# all flat_load / flat_store instructions replaced in place by the global forms (same encoding size, no code moves)
# baseline (speedup 1.0000x reference)
; #define LAS __attribute__((address_space(3)))
; __device__ __forceinline__ void p0_transpose_item(const float* W, int K, int N, bf16_t* WT, LAS float* scr, int item, int lane) {
;     const int nblk = N / 32, kb = item / nblk, nb = item % nblk, k0 = 64 * kb, n0 = 32 * nb;
;     float tv[32];
; #pragma unroll
;     for (int i = 0; i < 32; ++i) tv[i] = W[(size_t)(k0 + 2 * i + (lane >> 5)) * N + n0 + (lane & 31)];
.LBB0_9:
	s_mul_hi_i32 s41, s21, 0x532ae21d
	s_lshr_b32 s42, s41, 31
	s_ashr_i32 s41, s41, 6
	s_add_i32 s41, s41, s42
	s_lshl_b32 s44, s41, 6
	s_mulk_i32 s41, 0xe760
	s_add_i32 s42, s7, s41
	v_or_b32_e32 v2, s44, v5
	s_ashr_i32 s43, s42, 31
	v_or_b32_e32 v58, 12, v2
	v_or_b32_e32 v60, 14, v2
	v_or_b32_e32 v62, 16, v2
	v_or_b32_e32 v64, 18, v2
	v_or_b32_e32 v66, 20, v2
	v_or_b32_e32 v68, 22, v2
	v_or_b32_e32 v72, 24, v2
	v_or_b32_e32 v74, 26, v2
	v_or_b32_e32 v76, 28, v2
	v_or_b32_e32 v92, 30, v2
	v_or_b32_e32 v94, 32, v2
	v_or_b32_e32 v96, 34, v2
	v_or_b32_e32 v98, 36, v2
	v_lshl_add_u64 v[44:45], s[42:43], 2, v[40:41]
	v_or_b32_e32 v48, 2, v2
	v_or_b32_e32 v50, 4, v2
	v_or_b32_e32 v52, 6, v2
	v_or_b32_e32 v54, 8, v2
	v_or_b32_e32 v56, 10, v2
	v_or_b32_e32 v100, 38, v2
	v_or_b32_e32 v102, 40, v2
	v_or_b32_e32 v104, 42, v2
	v_or_b32_e32 v106, 44, v2
	v_or_b32_e32 v108, 46, v2
	v_or_b32_e32 v110, 48, v2
	v_or_b32_e32 v112, 50, v2
	v_or_b32_e32 v114, 52, v2
	v_or_b32_e32 v116, 54, v2
	v_or_b32_e32 v118, 56, v2
	v_or_b32_e32 v120, 58, v2
	v_or_b32_e32 v122, 60, v2
	v_or_b32_e32 v124, 62, v2
	v_mad_i64_i32 v[46:47], s[46:47], v2, s51, v[44:45]
	v_mad_i64_i32 v[58:59], s[46:47], v58, s51, v[44:45]
	v_mad_i64_i32 v[60:61], s[46:47], v60, s51, v[44:45]
	v_mad_i64_i32 v[62:63], s[46:47], v62, s51, v[44:45]
	v_mad_i64_i32 v[64:65], s[46:47], v64, s51, v[44:45]
	v_mad_i64_i32 v[66:67], s[46:47], v66, s51, v[44:45]
	v_mad_i64_i32 v[68:69], s[46:47], v68, s51, v[44:45]
	v_mad_i64_i32 v[72:73], s[46:47], v72, s51, v[44:45]
	v_mad_i64_i32 v[74:75], s[46:47], v74, s51, v[44:45]
	v_mad_i64_i32 v[76:77], s[46:47], v76, s51, v[44:45]
	v_mad_i64_i32 v[92:93], s[46:47], v92, s51, v[44:45]
	v_mad_i64_i32 v[94:95], s[46:47], v94, s51, v[44:45]
	v_mad_i64_i32 v[96:97], s[46:47], v96, s51, v[44:45]
	v_mad_i64_i32 v[98:99], s[46:47], v98, s51, v[44:45]
	v_mad_i64_i32 v[48:49], s[46:47], v48, s51, v[44:45]
	v_mad_i64_i32 v[50:51], s[46:47], v50, s51, v[44:45]
	v_mad_i64_i32 v[52:53], s[46:47], v52, s51, v[44:45]
	v_mad_i64_i32 v[54:55], s[46:47], v54, s51, v[44:45]
	v_mad_i64_i32 v[56:57], s[46:47], v56, s51, v[44:45]
	v_mad_i64_i32 v[100:101], s[46:47], v100, s51, v[44:45]
	v_mad_i64_i32 v[102:103], s[46:47], v102, s51, v[44:45]
	v_mad_i64_i32 v[104:105], s[46:47], v104, s51, v[44:45]
	v_mad_i64_i32 v[106:107], s[46:47], v106, s51, v[44:45]
	v_mad_i64_i32 v[108:109], s[46:47], v108, s51, v[44:45]
	v_mad_i64_i32 v[110:111], s[46:47], v110, s51, v[44:45]
	v_mad_i64_i32 v[112:113], s[46:47], v112, s51, v[44:45]
	v_mad_i64_i32 v[114:115], s[46:47], v114, s51, v[44:45]
	v_mad_i64_i32 v[116:117], s[46:47], v116, s51, v[44:45]
	v_mad_i64_i32 v[118:119], s[46:47], v118, s51, v[44:45]
	v_mad_i64_i32 v[120:121], s[46:47], v120, s51, v[44:45]
	v_mad_i64_i32 v[122:123], s[46:47], v122, s51, v[44:45]
	v_mad_i64_i32 v[44:45], s[46:47], v124, s51, v[44:45]
	global_load_dword v2, v[46:47], off
	global_load_dword v124, v[48:49], off
	global_load_dword v125, v[50:51], off
	global_load_dword v126, v[52:53], off
	global_load_dword v127, v[54:55], off
	global_load_dword v128, v[56:57], off
	s_nop 0
	global_load_dword v58, v[58:59], off
	s_nop 0
	global_load_dword v59, v[60:61], off
	s_nop 0
	global_load_dword v60, v[62:63], off
	global_load_dword v61, v[64:65], off
	s_nop 0
	global_load_dword v62, v[66:67], off
	global_load_dword v63, v[68:69], off
	global_load_dword v64, v[72:73], off
	global_load_dword v65, v[74:75], off
	s_nop 0
	global_load_dword v66, v[76:77], off
	global_load_dword v67, v[92:93], off
	global_load_dword v68, v[94:95], off
	global_load_dword v69, v[96:97], off
	global_load_dword v72, v[98:99], off
	global_load_dword v73, v[100:101], off
	global_load_dword v74, v[102:103], off
	global_load_dword v75, v[104:105], off
	global_load_dword v76, v[106:107], off
	global_load_dword v77, v[108:109], off
	global_load_dword v92, v[110:111], off
	global_load_dword v93, v[112:113], off
	global_load_dword v94, v[114:115], off
	global_load_dword v95, v[116:117], off
	global_load_dword v96, v[118:119], off
	global_load_dword v97, v[120:121], off
	global_load_dword v98, v[122:123], off
	global_load_dword v99, v[44:45], off
	v_add_u32_e32 v50, s42, v78
	v_add_u32_e32 v44, 8, v50
	s_ashr_i32 s45, s44, 31
	v_ashrrev_i32_e32 v45, 31, v44
	s_waitcnt vmcnt(0)
; #define LAS __attribute__((address_space(3)))
; __device__ __forceinline__ unsigned cvt_pk_bf16(float lo, float hi) { unsigned r; asm volatile("v_cvt_pk_bf16_f32 %0, %1, %2" : "=v"(r) : "v"(lo), "v"(hi)); return r; }
; __device__ __forceinline__ void p0_transpose_item(const float* W, int K, int N, bf16_t* WT, LAS float* scr, int item, int lane) {
;     ...
; #pragma unroll
;     for (int i = 0; i < 32; ++i) scr[(2 * i + (lane >> 5)) * 33 + (lane & 31)] = tv[i];
;     asm volatile("s_waitcnt lgkmcnt(0)" ::: "memory");
;     const int c = lane & 7;
; #pragma unroll
;     for (int j = 0; j < 4; ++j) { const int n = (lane >> 3) + 8 * j; const LAS float* s = scr + (8 * c) * 33 + n;
;         u32x4 o; o.x = cvt_pk_bf16(s[0 * 33], s[1 * 33]); o.y = cvt_pk_bf16(s[2 * 33], s[3 * 33]); o.z = cvt_pk_bf16(s[4 * 33], s[5 * 33]); o.w = cvt_pk_bf16(s[6 * 33], s[7 * 33]);
;         *(u32x4*)(WT + (size_t)(n0 + n) * K + k0 + 8 * c) = o; }
;     asm volatile("s_waitcnt lgkmcnt(0)" ::: "memory");
	ds_write2_b32 v71, v2, v124 offset1:66
	s_waitcnt vmcnt(28)
	ds_write2_b32 v71, v125, v126 offset0:132 offset1:198
	s_waitcnt vmcnt(26)
	ds_write2_b32 v81, v127, v128 offset0:8 offset1:74
	s_waitcnt vmcnt(24)
	ds_write2_b32 v81, v58, v59 offset0:140 offset1:206
	s_waitcnt vmcnt(22)
	ds_write2_b32 v82, v60, v61 offset0:16 offset1:82
	s_waitcnt vmcnt(20)
	ds_write2_b32 v82, v62, v63 offset0:148 offset1:214
	s_waitcnt vmcnt(18)
	ds_write2_b32 v83, v64, v65 offset0:24 offset1:90
	s_waitcnt vmcnt(16)
	ds_write2_b32 v83, v66, v67 offset0:156 offset1:222
	s_waitcnt vmcnt(14)
	ds_write2_b32 v84, v68, v69 offset0:32 offset1:98
	s_waitcnt vmcnt(12)
	ds_write2_b32 v84, v72, v73 offset0:164 offset1:230
	s_waitcnt vmcnt(10)
	ds_write2_b32 v85, v74, v75 offset0:40 offset1:106
	s_waitcnt vmcnt(8)
	ds_write2_b32 v85, v76, v77 offset0:172 offset1:238
	s_waitcnt vmcnt(6)
	ds_write2_b32 v86, v92, v93 offset0:48 offset1:114
	s_waitcnt vmcnt(4)
	ds_write2_b32 v86, v94, v95 offset0:180 offset1:246
	s_waitcnt vmcnt(2)
	ds_write2_b32 v87, v96, v97 offset0:56 offset1:122
	s_waitcnt vmcnt(0)
	ds_write2_b32 v87, v98, v99 offset0:188 offset1:254
	v_lshl_add_u64 v[48:49], s[44:45], 1, v[42:43]
	v_add_u32_e32 v46, 16, v50
	v_lshlrev_b64 v[44:45], 11, v[44:45]
	s_waitcnt lgkmcnt(0)
	v_ashrrev_i32_e32 v51, 31, v50
	v_ashrrev_i32_e32 v47, 31, v46
	v_lshl_add_u64 v[56:57], v[48:49], 0, v[44:45]
	ds_read2_b32 v[44:45], v79 offset1:33
	v_lshlrev_b64 v[52:53], 11, v[50:51]
	v_lshlrev_b64 v[54:55], 11, v[46:47]
	s_waitcnt lgkmcnt(0)
	v_cvt_pk_bf16_f32 v44, v44, v45
	ds_read2_b32 v[46:47], v79 offset0:66 offset1:99
	v_lshl_add_u64 v[52:53], v[48:49], 0, v[52:53]
	s_waitcnt lgkmcnt(0)
	v_cvt_pk_bf16_f32 v45, v46, v47
	ds_read2_b32 v[46:47], v79 offset0:132 offset1:165
	s_waitcnt lgkmcnt(0)
	v_cvt_pk_bf16_f32 v46, v46, v47
	ds_read2_b32 v[58:59], v79 offset0:198 offset1:231
	s_waitcnt lgkmcnt(0)
	v_cvt_pk_bf16_f32 v47, v58, v59
	global_store_dwordx4 v[52:53], v[44:47], off
	ds_read2_b32 v[44:45], v79 offset0:8 offset1:41
	v_lshl_add_u64 v[54:55], v[48:49], 0, v[54:55]
	s_waitcnt lgkmcnt(0)
	v_cvt_pk_bf16_f32 v44, v44, v45
	ds_read2_b32 v[46:47], v79 offset0:74 offset1:107
	s_waitcnt lgkmcnt(0)
	v_cvt_pk_bf16_f32 v45, v46, v47
	ds_read2_b32 v[46:47], v79 offset0:140 offset1:173
	s_waitcnt lgkmcnt(0)
	v_cvt_pk_bf16_f32 v46, v46, v47
	ds_read2_b32 v[52:53], v79 offset0:206 offset1:239
	s_waitcnt lgkmcnt(0)
	v_cvt_pk_bf16_f32 v47, v52, v53
	global_store_dwordx4 v[56:57], v[44:47], off
	ds_read2_b32 v[44:45], v79 offset0:16 offset1:49
	v_add_u32_e32 v50, 24, v50
	s_waitcnt lgkmcnt(0)
	v_cvt_pk_bf16_f32 v44, v44, v45
	ds_read2_b32 v[46:47], v79 offset0:82 offset1:115
	s_waitcnt lgkmcnt(0)
	v_cvt_pk_bf16_f32 v45, v46, v47
	ds_read2_b32 v[46:47], v79 offset0:148 offset1:181
	s_waitcnt lgkmcnt(0)
	v_cvt_pk_bf16_f32 v46, v46, v47
	ds_read2_b32 v[52:53], v79 offset0:214 offset1:247
	s_waitcnt lgkmcnt(0)
	v_cvt_pk_bf16_f32 v47, v52, v53
	global_store_dwordx4 v[54:55], v[44:47], off
	ds_read2_b32 v[44:45], v79 offset0:24 offset1:57
	v_ashrrev_i32_e32 v51, 31, v50
	s_waitcnt lgkmcnt(0)
	v_cvt_pk_bf16_f32 v44, v44, v45
	ds_read2_b32 v[46:47], v79 offset0:90 offset1:123
	v_lshlrev_b64 v[50:51], 11, v[50:51]
	s_waitcnt lgkmcnt(0)
	v_cvt_pk_bf16_f32 v45, v46, v47
	ds_read2_b32 v[46:47], v79 offset0:156 offset1:189
	v_lshl_add_u64 v[48:49], v[48:49], 0, v[50:51]
	s_waitcnt lgkmcnt(0)
	v_cvt_pk_bf16_f32 v46, v46, v47
	ds_read2_b32 v[52:53], v79 offset0:222 offset1:255
	s_waitcnt lgkmcnt(0)
	v_cvt_pk_bf16_f32 v47, v52, v53
	global_store_dwordx4 v[48:49], v[44:47], off
	s_waitcnt lgkmcnt(0)
	s_add_i32 s21, s21, s60
	s_add_i32 s7, s7, s8
	s_cmpk_gt_i32 s21, 0xc4f
	s_cbranch_scc0 .LBB0_9

; #define LAS __attribute__((address_space(3)))
; __device__ __forceinline__ void p0_transpose_item(const float* W, int K, int N, bf16_t* WT, LAS float* scr, int item, int lane) {
;     const int nblk = N / 32, kb = item / nblk, nb = item % nblk, k0 = 64 * kb, n0 = 32 * nb;
;     float tv[32];
; #pragma unroll
;     for (int i = 0; i < 32; ++i) tv[i] = W[(size_t)(k0 + 2 * i + (lane >> 5)) * N + n0 + (lane & 31)];
.LBB0_14:
	s_ashr_i32 s42, s46, 31
	s_lshr_b32 s42, s42, 27
	s_add_i32 s42, s46, s42
	s_ashr_i32 s42, s42, 5
	s_lshl_b32 s44, s42, 6
	s_lshl_b32 s42, s42, 10
	v_or_b32_e32 v54, s44, v5
	s_sub_i32 s42, s8, s42
	v_or_b32_e32 v58, 14, v54
	v_or_b32_e32 v60, 16, v54
	v_or_b32_e32 v62, 18, v54
	v_or_b32_e32 v64, 20, v54
	v_or_b32_e32 v66, 22, v54
	v_or_b32_e32 v68, 24, v54
	v_or_b32_e32 v72, 26, v54
	v_or_b32_e32 v74, 28, v54
	v_or_b32_e32 v76, 30, v54
	v_or_b32_e32 v92, 32, v54
	v_or_b32_e32 v94, 34, v54
	v_or_b32_e32 v96, 36, v54
	v_or_b32_e32 v98, 38, v54
	s_ashr_i32 s43, s42, 31
	v_ashrrev_i32_e32 v55, 31, v54
	v_or_b32_e32 v44, 2, v54
	v_or_b32_e32 v46, 4, v54
	v_or_b32_e32 v48, 6, v54
	v_or_b32_e32 v50, 8, v54
	v_or_b32_e32 v52, 10, v54
	v_or_b32_e32 v56, 12, v54
	v_or_b32_e32 v100, 40, v54
	v_or_b32_e32 v102, 42, v54
	v_or_b32_e32 v104, 44, v54
	v_or_b32_e32 v106, 46, v54
	v_or_b32_e32 v108, 48, v54
	v_or_b32_e32 v110, 50, v54
	v_or_b32_e32 v112, 52, v54
	v_or_b32_e32 v114, 54, v54
	v_or_b32_e32 v116, 56, v54
	v_or_b32_e32 v118, 58, v54
	v_or_b32_e32 v120, 60, v54
	v_or_b32_e32 v122, 62, v54
	v_ashrrev_i32_e32 v59, 31, v58
	v_ashrrev_i32_e32 v61, 31, v60
	v_ashrrev_i32_e32 v63, 31, v62
	v_ashrrev_i32_e32 v65, 31, v64
	v_ashrrev_i32_e32 v67, 31, v66
	v_ashrrev_i32_e32 v69, 31, v68
	v_ashrrev_i32_e32 v73, 31, v72
	v_ashrrev_i32_e32 v75, 31, v74
	v_ashrrev_i32_e32 v77, 31, v76
	v_ashrrev_i32_e32 v93, 31, v92
	v_ashrrev_i32_e32 v95, 31, v94
	v_ashrrev_i32_e32 v97, 31, v96
	v_ashrrev_i32_e32 v99, 31, v98
	v_lshl_add_u64 v[124:125], s[42:43], 2, v[40:41]
	v_lshlrev_b64 v[54:55], 12, v[54:55]
	v_ashrrev_i32_e32 v45, 31, v44
	v_ashrrev_i32_e32 v47, 31, v46
	v_ashrrev_i32_e32 v49, 31, v48
	v_ashrrev_i32_e32 v51, 31, v50
	v_ashrrev_i32_e32 v53, 31, v52
	v_ashrrev_i32_e32 v57, 31, v56
	v_ashrrev_i32_e32 v101, 31, v100
	v_ashrrev_i32_e32 v103, 31, v102
	v_ashrrev_i32_e32 v105, 31, v104
	v_ashrrev_i32_e32 v107, 31, v106
	v_ashrrev_i32_e32 v109, 31, v108
	v_ashrrev_i32_e32 v111, 31, v110
	v_ashrrev_i32_e32 v113, 31, v112
	v_ashrrev_i32_e32 v115, 31, v114
	v_ashrrev_i32_e32 v117, 31, v116
	v_ashrrev_i32_e32 v119, 31, v118
	v_ashrrev_i32_e32 v121, 31, v120
	v_ashrrev_i32_e32 v123, 31, v122
	v_lshlrev_b64 v[58:59], 12, v[58:59]
	v_lshlrev_b64 v[60:61], 12, v[60:61]
	v_lshlrev_b64 v[62:63], 12, v[62:63]
	v_lshlrev_b64 v[64:65], 12, v[64:65]
	v_lshlrev_b64 v[66:67], 12, v[66:67]
	v_lshlrev_b64 v[68:69], 12, v[68:69]
	v_lshlrev_b64 v[72:73], 12, v[72:73]
	v_lshlrev_b64 v[74:75], 12, v[74:75]
	v_lshlrev_b64 v[76:77], 12, v[76:77]
	v_lshlrev_b64 v[92:93], 12, v[92:93]
	v_lshlrev_b64 v[94:95], 12, v[94:95]
	v_lshlrev_b64 v[96:97], 12, v[96:97]
	v_lshlrev_b64 v[98:99], 12, v[98:99]
	v_lshl_add_u64 v[54:55], v[124:125], 0, v[54:55]
	v_lshlrev_b64 v[44:45], 12, v[44:45]
	v_lshlrev_b64 v[46:47], 12, v[46:47]
	v_lshlrev_b64 v[48:49], 12, v[48:49]
	v_lshlrev_b64 v[50:51], 12, v[50:51]
	v_lshlrev_b64 v[52:53], 12, v[52:53]
	v_lshlrev_b64 v[56:57], 12, v[56:57]
	v_lshlrev_b64 v[100:101], 12, v[100:101]
	v_lshlrev_b64 v[102:103], 12, v[102:103]
	v_lshlrev_b64 v[104:105], 12, v[104:105]
	v_lshlrev_b64 v[106:107], 12, v[106:107]
	v_lshlrev_b64 v[108:109], 12, v[108:109]
	v_lshlrev_b64 v[110:111], 12, v[110:111]
	v_lshlrev_b64 v[112:113], 12, v[112:113]
	v_lshlrev_b64 v[114:115], 12, v[114:115]
	v_lshlrev_b64 v[116:117], 12, v[116:117]
	v_lshlrev_b64 v[118:119], 12, v[118:119]
	v_lshlrev_b64 v[120:121], 12, v[120:121]
	v_lshlrev_b64 v[122:123], 12, v[122:123]
	v_lshl_add_u64 v[58:59], v[124:125], 0, v[58:59]
	v_lshl_add_u64 v[60:61], v[124:125], 0, v[60:61]
	v_lshl_add_u64 v[62:63], v[124:125], 0, v[62:63]
	v_lshl_add_u64 v[64:65], v[124:125], 0, v[64:65]
	v_lshl_add_u64 v[66:67], v[124:125], 0, v[66:67]
	v_lshl_add_u64 v[68:69], v[124:125], 0, v[68:69]
	v_lshl_add_u64 v[72:73], v[124:125], 0, v[72:73]
	v_lshl_add_u64 v[74:75], v[124:125], 0, v[74:75]
	v_lshl_add_u64 v[76:77], v[124:125], 0, v[76:77]
	v_lshl_add_u64 v[92:93], v[124:125], 0, v[92:93]
	v_lshl_add_u64 v[94:95], v[124:125], 0, v[94:95]
	v_lshl_add_u64 v[96:97], v[124:125], 0, v[96:97]
	v_lshl_add_u64 v[98:99], v[124:125], 0, v[98:99]
	v_lshl_add_u64 v[44:45], v[124:125], 0, v[44:45]
	v_lshl_add_u64 v[46:47], v[124:125], 0, v[46:47]
	v_lshl_add_u64 v[48:49], v[124:125], 0, v[48:49]
	v_lshl_add_u64 v[50:51], v[124:125], 0, v[50:51]
	v_lshl_add_u64 v[52:53], v[124:125], 0, v[52:53]
	v_lshl_add_u64 v[56:57], v[124:125], 0, v[56:57]
	v_lshl_add_u64 v[100:101], v[124:125], 0, v[100:101]
	v_lshl_add_u64 v[102:103], v[124:125], 0, v[102:103]
	v_lshl_add_u64 v[104:105], v[124:125], 0, v[104:105]
	v_lshl_add_u64 v[106:107], v[124:125], 0, v[106:107]
	v_lshl_add_u64 v[108:109], v[124:125], 0, v[108:109]
	v_lshl_add_u64 v[110:111], v[124:125], 0, v[110:111]
	v_lshl_add_u64 v[112:113], v[124:125], 0, v[112:113]
	v_lshl_add_u64 v[114:115], v[124:125], 0, v[114:115]
	v_lshl_add_u64 v[116:117], v[124:125], 0, v[116:117]
	v_lshl_add_u64 v[118:119], v[124:125], 0, v[118:119]
	v_lshl_add_u64 v[120:121], v[124:125], 0, v[120:121]
	v_lshl_add_u64 v[122:123], v[124:125], 0, v[122:123]
	global_load_dword v2, v[54:55], off
	global_load_dword v124, v[44:45], off
	global_load_dword v125, v[46:47], off
	global_load_dword v126, v[48:49], off
	global_load_dword v127, v[50:51], off
	global_load_dword v128, v[52:53], off
	global_load_dword v129, v[56:57], off
	s_nop 0
	global_load_dword v58, v[58:59], off
	s_nop 0
	global_load_dword v59, v[60:61], off
	s_nop 0
	global_load_dword v60, v[62:63], off
	global_load_dword v61, v[64:65], off
	s_nop 0
	global_load_dword v62, v[66:67], off
	global_load_dword v63, v[68:69], off
	global_load_dword v64, v[72:73], off
	global_load_dword v65, v[74:75], off
	s_nop 0
	global_load_dword v66, v[76:77], off
	global_load_dword v67, v[92:93], off
	global_load_dword v68, v[94:95], off
	global_load_dword v69, v[96:97], off
	global_load_dword v72, v[98:99], off
	global_load_dword v73, v[100:101], off
	global_load_dword v74, v[102:103], off
	global_load_dword v75, v[104:105], off
	global_load_dword v76, v[106:107], off
	global_load_dword v77, v[108:109], off
	global_load_dword v92, v[110:111], off
	global_load_dword v93, v[112:113], off
	global_load_dword v94, v[114:115], off
	global_load_dword v95, v[116:117], off
	global_load_dword v96, v[118:119], off
	global_load_dword v97, v[120:121], off
	global_load_dword v98, v[122:123], off
	v_add_u32_e32 v50, s42, v78
	v_add_u32_e32 v46, 8, v50
	s_ashr_i32 s45, s44, 31
	v_ashrrev_i32_e32 v47, 31, v46
	s_waitcnt vmcnt(0)
; #define LAS __attribute__((address_space(3)))
; __device__ __forceinline__ unsigned cvt_pk_bf16(float lo, float hi) { unsigned r; asm volatile("v_cvt_pk_bf16_f32 %0, %1, %2" : "=v"(r) : "v"(lo), "v"(hi)); return r; }
; __device__ __forceinline__ void p0_transpose_item(const float* W, int K, int N, bf16_t* WT, LAS float* scr, int item, int lane) {
;     ...
; #pragma unroll
;     for (int i = 0; i < 32; ++i) scr[(2 * i + (lane >> 5)) * 33 + (lane & 31)] = tv[i];
;     asm volatile("s_waitcnt lgkmcnt(0)" ::: "memory");
;     const int c = lane & 7;
; #pragma unroll
;     for (int j = 0; j < 4; ++j) { const int n = (lane >> 3) + 8 * j; const LAS float* s = scr + (8 * c) * 33 + n;
;         u32x4 o; o.x = cvt_pk_bf16(s[0 * 33], s[1 * 33]); o.y = cvt_pk_bf16(s[2 * 33], s[3 * 33]); o.z = cvt_pk_bf16(s[4 * 33], s[5 * 33]); o.w = cvt_pk_bf16(s[6 * 33], s[7 * 33]);
;         *(u32x4*)(WT + (size_t)(n0 + n) * K + k0 + 8 * c) = o; }
;     asm volatile("s_waitcnt lgkmcnt(0)" ::: "memory");
	ds_write2_b32 v71, v2, v124 offset1:66
	ds_write2_b32 v71, v125, v126 offset0:132 offset1:198
	ds_write2_b32 v81, v127, v128 offset0:8 offset1:74
	ds_write2_b32 v81, v129, v58 offset0:140 offset1:206
	ds_write2_b32 v82, v59, v60 offset0:16 offset1:82
	ds_write2_b32 v82, v61, v62 offset0:148 offset1:214
	ds_write2_b32 v83, v63, v64 offset0:24 offset1:90
	ds_write2_b32 v83, v65, v66 offset0:156 offset1:222
	ds_write2_b32 v84, v67, v68 offset0:32 offset1:98
	ds_write2_b32 v84, v69, v72 offset0:164 offset1:230
	ds_write2_b32 v85, v73, v74 offset0:40 offset1:106
	ds_write2_b32 v85, v75, v76 offset0:172 offset1:238
	ds_write2_b32 v86, v77, v92 offset0:48 offset1:114
	ds_write2_b32 v86, v93, v94 offset0:180 offset1:246
	ds_write2_b32 v87, v95, v96 offset0:56 offset1:122
	ds_write2_b32 v87, v97, v98 offset0:188 offset1:254
	v_lshl_add_u64 v[44:45], s[44:45], 1, v[42:43]
	v_add_u32_e32 v48, 16, v50
	v_lshlrev_b64 v[46:47], 9, v[46:47]
	s_waitcnt lgkmcnt(0)
	v_ashrrev_i32_e32 v51, 31, v50
	v_ashrrev_i32_e32 v49, 31, v48
	v_lshl_add_u64 v[56:57], v[44:45], 0, v[46:47]
	ds_read2_b32 v[46:47], v79 offset1:33
	v_lshlrev_b64 v[52:53], 9, v[50:51]
	v_lshlrev_b64 v[54:55], 9, v[48:49]
	s_waitcnt lgkmcnt(0)
	v_cvt_pk_bf16_f32 v46, v46, v47
	ds_read2_b32 v[48:49], v79 offset0:66 offset1:99
	v_lshl_add_u64 v[52:53], v[44:45], 0, v[52:53]
	s_waitcnt lgkmcnt(0)
	v_cvt_pk_bf16_f32 v47, v48, v49
	ds_read2_b32 v[48:49], v79 offset0:132 offset1:165
	s_waitcnt lgkmcnt(0)
	v_cvt_pk_bf16_f32 v48, v48, v49
	ds_read2_b32 v[58:59], v79 offset0:198 offset1:231
	s_waitcnt lgkmcnt(0)
	v_cvt_pk_bf16_f32 v49, v58, v59
	global_store_dwordx4 v[52:53], v[46:49], off
	ds_read2_b32 v[46:47], v79 offset0:8 offset1:41
	v_lshl_add_u64 v[54:55], v[44:45], 0, v[54:55]
	s_waitcnt lgkmcnt(0)
	v_cvt_pk_bf16_f32 v46, v46, v47
	ds_read2_b32 v[48:49], v79 offset0:74 offset1:107
	s_waitcnt lgkmcnt(0)
	v_cvt_pk_bf16_f32 v47, v48, v49
	ds_read2_b32 v[48:49], v79 offset0:140 offset1:173
	s_waitcnt lgkmcnt(0)
	v_cvt_pk_bf16_f32 v48, v48, v49
	ds_read2_b32 v[52:53], v79 offset0:206 offset1:239
	s_waitcnt lgkmcnt(0)
	v_cvt_pk_bf16_f32 v49, v52, v53
	global_store_dwordx4 v[56:57], v[46:49], off
	ds_read2_b32 v[46:47], v79 offset0:16 offset1:49
	v_add_u32_e32 v50, 24, v50
	s_waitcnt lgkmcnt(0)
	v_cvt_pk_bf16_f32 v46, v46, v47
	ds_read2_b32 v[48:49], v79 offset0:82 offset1:115
	s_waitcnt lgkmcnt(0)
	v_cvt_pk_bf16_f32 v47, v48, v49
	ds_read2_b32 v[48:49], v79 offset0:148 offset1:181
	s_waitcnt lgkmcnt(0)
	v_cvt_pk_bf16_f32 v48, v48, v49
	ds_read2_b32 v[52:53], v79 offset0:214 offset1:247
	s_waitcnt lgkmcnt(0)
	v_cvt_pk_bf16_f32 v49, v52, v53
	global_store_dwordx4 v[54:55], v[46:49], off
	ds_read2_b32 v[46:47], v79 offset0:24 offset1:57
	v_ashrrev_i32_e32 v51, 31, v50
	s_waitcnt lgkmcnt(0)
	v_cvt_pk_bf16_f32 v46, v46, v47
	ds_read2_b32 v[48:49], v79 offset0:90 offset1:123
	v_lshlrev_b64 v[50:51], 9, v[50:51]
	s_waitcnt lgkmcnt(0)
	v_cvt_pk_bf16_f32 v47, v48, v49
	ds_read2_b32 v[48:49], v79 offset0:156 offset1:189
	v_lshl_add_u64 v[44:45], v[44:45], 0, v[50:51]
	s_waitcnt lgkmcnt(0)
	v_cvt_pk_bf16_f32 v48, v48, v49
	ds_read2_b32 v[52:53], v79 offset0:222 offset1:255
	s_waitcnt lgkmcnt(0)
	v_cvt_pk_bf16_f32 v49, v52, v53
	global_store_dwordx4 v[44:45], v[46:49], off
	s_waitcnt lgkmcnt(0)
	s_add_i32 s46, s46, s60
	s_add_i32 s8, s8, s41
	s_cmpk_gt_i32 s46, 0x7f
	s_cbranch_scc0 .LBB0_14
	s_branch .LBB0_11

; #define LAS __attribute__((address_space(3)))
; __device__ __forceinline__ void p0_transpose_item(const float* W, int K, int N, bf16_t* WT, LAS float* scr, int item, int lane) {
;     const int nblk = N / 32, kb = item / nblk, nb = item % nblk, k0 = 64 * kb, n0 = 32 * nb;
;     float tv[32];
; #pragma unroll
;     for (int i = 0; i < 32; ++i) tv[i] = W[(size_t)(k0 + 2 * i + (lane >> 5)) * N + n0 + (lane & 31)];
.LBB0_17:
	s_ashr_i32 s42, s41, 31
	s_lshr_b32 s42, s42, 27
	s_add_i32 s42, s41, s42
	s_ashr_i32 s42, s42, 5
	s_lshl_b32 s44, s42, 6
	s_lshl_b32 s42, s42, 10
	v_or_b32_e32 v54, s44, v5
	s_sub_i32 s42, s7, s42
	v_or_b32_e32 v58, 14, v54
	v_or_b32_e32 v60, 16, v54
	v_or_b32_e32 v62, 18, v54
	v_or_b32_e32 v64, 20, v54
	v_or_b32_e32 v66, 22, v54
	v_or_b32_e32 v68, 24, v54
	v_or_b32_e32 v72, 26, v54
	v_or_b32_e32 v74, 28, v54
	v_or_b32_e32 v76, 30, v54
	v_or_b32_e32 v92, 32, v54
	v_or_b32_e32 v94, 34, v54
	v_or_b32_e32 v96, 36, v54
	v_or_b32_e32 v98, 38, v54
	s_ashr_i32 s43, s42, 31
	v_ashrrev_i32_e32 v55, 31, v54
	v_or_b32_e32 v44, 2, v54
	v_or_b32_e32 v46, 4, v54
	v_or_b32_e32 v48, 6, v54
	v_or_b32_e32 v50, 8, v54
	v_or_b32_e32 v52, 10, v54
	v_or_b32_e32 v56, 12, v54
	v_or_b32_e32 v100, 40, v54
	v_or_b32_e32 v102, 42, v54
	v_or_b32_e32 v104, 44, v54
	v_or_b32_e32 v106, 46, v54
	v_or_b32_e32 v108, 48, v54
	v_or_b32_e32 v110, 50, v54
	v_or_b32_e32 v112, 52, v54
	v_or_b32_e32 v114, 54, v54
	v_or_b32_e32 v116, 56, v54
	v_or_b32_e32 v118, 58, v54
	v_or_b32_e32 v120, 60, v54
	v_or_b32_e32 v122, 62, v54
	v_ashrrev_i32_e32 v59, 31, v58
	v_ashrrev_i32_e32 v61, 31, v60
	v_ashrrev_i32_e32 v63, 31, v62
	v_ashrrev_i32_e32 v65, 31, v64
	v_ashrrev_i32_e32 v67, 31, v66
	v_ashrrev_i32_e32 v69, 31, v68
	v_ashrrev_i32_e32 v73, 31, v72
	v_ashrrev_i32_e32 v75, 31, v74
	v_ashrrev_i32_e32 v77, 31, v76
	v_ashrrev_i32_e32 v93, 31, v92
	v_ashrrev_i32_e32 v95, 31, v94
	v_ashrrev_i32_e32 v97, 31, v96
	v_ashrrev_i32_e32 v99, 31, v98
	v_lshl_add_u64 v[124:125], s[42:43], 2, v[40:41]
	v_lshlrev_b64 v[54:55], 12, v[54:55]
	v_ashrrev_i32_e32 v45, 31, v44
	v_ashrrev_i32_e32 v47, 31, v46
	v_ashrrev_i32_e32 v49, 31, v48
	v_ashrrev_i32_e32 v51, 31, v50
	v_ashrrev_i32_e32 v53, 31, v52
	v_ashrrev_i32_e32 v57, 31, v56
	v_ashrrev_i32_e32 v101, 31, v100
	v_ashrrev_i32_e32 v103, 31, v102
	v_ashrrev_i32_e32 v105, 31, v104
	v_ashrrev_i32_e32 v107, 31, v106
	v_ashrrev_i32_e32 v109, 31, v108
	v_ashrrev_i32_e32 v111, 31, v110
	v_ashrrev_i32_e32 v113, 31, v112
	v_ashrrev_i32_e32 v115, 31, v114
	v_ashrrev_i32_e32 v117, 31, v116
	v_ashrrev_i32_e32 v119, 31, v118
	v_ashrrev_i32_e32 v121, 31, v120
	v_ashrrev_i32_e32 v123, 31, v122
	v_lshlrev_b64 v[58:59], 12, v[58:59]
	v_lshlrev_b64 v[60:61], 12, v[60:61]
	v_lshlrev_b64 v[62:63], 12, v[62:63]
	v_lshlrev_b64 v[64:65], 12, v[64:65]
	v_lshlrev_b64 v[66:67], 12, v[66:67]
	v_lshlrev_b64 v[68:69], 12, v[68:69]
	v_lshlrev_b64 v[72:73], 12, v[72:73]
	v_lshlrev_b64 v[74:75], 12, v[74:75]
	v_lshlrev_b64 v[76:77], 12, v[76:77]
	v_lshlrev_b64 v[92:93], 12, v[92:93]
	v_lshlrev_b64 v[94:95], 12, v[94:95]
	v_lshlrev_b64 v[96:97], 12, v[96:97]
	v_lshlrev_b64 v[98:99], 12, v[98:99]
	v_lshl_add_u64 v[54:55], v[124:125], 0, v[54:55]
	v_lshlrev_b64 v[44:45], 12, v[44:45]
	v_lshlrev_b64 v[46:47], 12, v[46:47]
	v_lshlrev_b64 v[48:49], 12, v[48:49]
	v_lshlrev_b64 v[50:51], 12, v[50:51]
	v_lshlrev_b64 v[52:53], 12, v[52:53]
	v_lshlrev_b64 v[56:57], 12, v[56:57]
	v_lshlrev_b64 v[100:101], 12, v[100:101]
	v_lshlrev_b64 v[102:103], 12, v[102:103]
	v_lshlrev_b64 v[104:105], 12, v[104:105]
	v_lshlrev_b64 v[106:107], 12, v[106:107]
	v_lshlrev_b64 v[108:109], 12, v[108:109]
	v_lshlrev_b64 v[110:111], 12, v[110:111]
	v_lshlrev_b64 v[112:113], 12, v[112:113]
	v_lshlrev_b64 v[114:115], 12, v[114:115]
	v_lshlrev_b64 v[116:117], 12, v[116:117]
	v_lshlrev_b64 v[118:119], 12, v[118:119]
	v_lshlrev_b64 v[120:121], 12, v[120:121]
	v_lshlrev_b64 v[122:123], 12, v[122:123]
	v_lshl_add_u64 v[58:59], v[124:125], 0, v[58:59]
	v_lshl_add_u64 v[60:61], v[124:125], 0, v[60:61]
	v_lshl_add_u64 v[62:63], v[124:125], 0, v[62:63]
	v_lshl_add_u64 v[64:65], v[124:125], 0, v[64:65]
	v_lshl_add_u64 v[66:67], v[124:125], 0, v[66:67]
	v_lshl_add_u64 v[68:69], v[124:125], 0, v[68:69]
	v_lshl_add_u64 v[72:73], v[124:125], 0, v[72:73]
	v_lshl_add_u64 v[74:75], v[124:125], 0, v[74:75]
	v_lshl_add_u64 v[76:77], v[124:125], 0, v[76:77]
	v_lshl_add_u64 v[92:93], v[124:125], 0, v[92:93]
	v_lshl_add_u64 v[94:95], v[124:125], 0, v[94:95]
	v_lshl_add_u64 v[96:97], v[124:125], 0, v[96:97]
	v_lshl_add_u64 v[98:99], v[124:125], 0, v[98:99]
	v_lshl_add_u64 v[44:45], v[124:125], 0, v[44:45]
	v_lshl_add_u64 v[46:47], v[124:125], 0, v[46:47]
	v_lshl_add_u64 v[48:49], v[124:125], 0, v[48:49]
	v_lshl_add_u64 v[50:51], v[124:125], 0, v[50:51]
	v_lshl_add_u64 v[52:53], v[124:125], 0, v[52:53]
	v_lshl_add_u64 v[56:57], v[124:125], 0, v[56:57]
	v_lshl_add_u64 v[100:101], v[124:125], 0, v[100:101]
	v_lshl_add_u64 v[102:103], v[124:125], 0, v[102:103]
	v_lshl_add_u64 v[104:105], v[124:125], 0, v[104:105]
	v_lshl_add_u64 v[106:107], v[124:125], 0, v[106:107]
	v_lshl_add_u64 v[108:109], v[124:125], 0, v[108:109]
	v_lshl_add_u64 v[110:111], v[124:125], 0, v[110:111]
	v_lshl_add_u64 v[112:113], v[124:125], 0, v[112:113]
	v_lshl_add_u64 v[114:115], v[124:125], 0, v[114:115]
	v_lshl_add_u64 v[116:117], v[124:125], 0, v[116:117]
	v_lshl_add_u64 v[118:119], v[124:125], 0, v[118:119]
	v_lshl_add_u64 v[120:121], v[124:125], 0, v[120:121]
	v_lshl_add_u64 v[122:123], v[124:125], 0, v[122:123]
	global_load_dword v2, v[54:55], off
	global_load_dword v124, v[44:45], off
	global_load_dword v125, v[46:47], off
	global_load_dword v126, v[48:49], off
	global_load_dword v127, v[50:51], off
	global_load_dword v128, v[52:53], off
	global_load_dword v129, v[56:57], off
	s_nop 0
	global_load_dword v58, v[58:59], off
	s_nop 0
	global_load_dword v59, v[60:61], off
	s_nop 0
	global_load_dword v60, v[62:63], off
	global_load_dword v61, v[64:65], off
	s_nop 0
	global_load_dword v62, v[66:67], off
	global_load_dword v63, v[68:69], off
	global_load_dword v64, v[72:73], off
	global_load_dword v65, v[74:75], off
	s_nop 0
	global_load_dword v66, v[76:77], off
	global_load_dword v67, v[92:93], off
	global_load_dword v68, v[94:95], off
	global_load_dword v69, v[96:97], off
	global_load_dword v72, v[98:99], off
	global_load_dword v73, v[100:101], off
	global_load_dword v74, v[102:103], off
	global_load_dword v75, v[104:105], off
	global_load_dword v76, v[106:107], off
	global_load_dword v77, v[108:109], off
	global_load_dword v92, v[110:111], off
	global_load_dword v93, v[112:113], off
	global_load_dword v94, v[114:115], off
	global_load_dword v95, v[116:117], off
	global_load_dword v96, v[118:119], off
	global_load_dword v97, v[120:121], off
	global_load_dword v98, v[122:123], off
	v_add_u32_e32 v50, s42, v78
	v_add_u32_e32 v46, 8, v50
	s_ashr_i32 s45, s44, 31
	v_ashrrev_i32_e32 v47, 31, v46
	s_waitcnt vmcnt(0)
; #define LAS __attribute__((address_space(3)))
; __device__ __forceinline__ unsigned cvt_pk_bf16(float lo, float hi) { unsigned r; asm volatile("v_cvt_pk_bf16_f32 %0, %1, %2" : "=v"(r) : "v"(lo), "v"(hi)); return r; }
; __device__ __forceinline__ void p0_transpose_item(const float* W, int K, int N, bf16_t* WT, LAS float* scr, int item, int lane) {
;     ...
; #pragma unroll
;     for (int i = 0; i < 32; ++i) scr[(2 * i + (lane >> 5)) * 33 + (lane & 31)] = tv[i];
;     asm volatile("s_waitcnt lgkmcnt(0)" ::: "memory");
;     const int c = lane & 7;
; #pragma unroll
;     for (int j = 0; j < 4; ++j) { const int n = (lane >> 3) + 8 * j; const LAS float* s = scr + (8 * c) * 33 + n;
;         u32x4 o; o.x = cvt_pk_bf16(s[0 * 33], s[1 * 33]); o.y = cvt_pk_bf16(s[2 * 33], s[3 * 33]); o.z = cvt_pk_bf16(s[4 * 33], s[5 * 33]); o.w = cvt_pk_bf16(s[6 * 33], s[7 * 33]);
;         *(u32x4*)(WT + (size_t)(n0 + n) * K + k0 + 8 * c) = o; }
;     asm volatile("s_waitcnt lgkmcnt(0)" ::: "memory");
	ds_write2_b32 v71, v2, v124 offset1:66
	ds_write2_b32 v71, v125, v126 offset0:132 offset1:198
	ds_write2_b32 v81, v127, v128 offset0:8 offset1:74
	ds_write2_b32 v81, v129, v58 offset0:140 offset1:206
	ds_write2_b32 v82, v59, v60 offset0:16 offset1:82
	ds_write2_b32 v82, v61, v62 offset0:148 offset1:214
	ds_write2_b32 v83, v63, v64 offset0:24 offset1:90
	ds_write2_b32 v83, v65, v66 offset0:156 offset1:222
	ds_write2_b32 v84, v67, v68 offset0:32 offset1:98
	ds_write2_b32 v84, v69, v72 offset0:164 offset1:230
	ds_write2_b32 v85, v73, v74 offset0:40 offset1:106
	ds_write2_b32 v85, v75, v76 offset0:172 offset1:238
	ds_write2_b32 v86, v77, v92 offset0:48 offset1:114
	ds_write2_b32 v86, v93, v94 offset0:180 offset1:246
	ds_write2_b32 v87, v95, v96 offset0:56 offset1:122
	ds_write2_b32 v87, v97, v98 offset0:188 offset1:254
	v_lshl_add_u64 v[44:45], s[44:45], 1, v[42:43]
	v_add_u32_e32 v48, 16, v50
	v_lshlrev_b64 v[46:47], 11, v[46:47]
	s_waitcnt lgkmcnt(0)
	v_ashrrev_i32_e32 v51, 31, v50
	v_ashrrev_i32_e32 v49, 31, v48
	v_lshl_add_u64 v[56:57], v[44:45], 0, v[46:47]
	ds_read2_b32 v[46:47], v79 offset1:33
	v_lshlrev_b64 v[52:53], 11, v[50:51]
	v_lshlrev_b64 v[54:55], 11, v[48:49]
	s_waitcnt lgkmcnt(0)
	v_cvt_pk_bf16_f32 v46, v46, v47
	ds_read2_b32 v[48:49], v79 offset0:66 offset1:99
	v_lshl_add_u64 v[52:53], v[44:45], 0, v[52:53]
	s_waitcnt lgkmcnt(0)
	v_cvt_pk_bf16_f32 v47, v48, v49
	ds_read2_b32 v[48:49], v79 offset0:132 offset1:165
	s_waitcnt lgkmcnt(0)
	v_cvt_pk_bf16_f32 v48, v48, v49
	ds_read2_b32 v[58:59], v79 offset0:198 offset1:231
	s_waitcnt lgkmcnt(0)
	v_cvt_pk_bf16_f32 v49, v58, v59
	global_store_dwordx4 v[52:53], v[46:49], off
	ds_read2_b32 v[46:47], v79 offset0:8 offset1:41
	v_lshl_add_u64 v[54:55], v[44:45], 0, v[54:55]
	s_waitcnt lgkmcnt(0)
	v_cvt_pk_bf16_f32 v46, v46, v47
	ds_read2_b32 v[48:49], v79 offset0:74 offset1:107
	s_waitcnt lgkmcnt(0)
	v_cvt_pk_bf16_f32 v47, v48, v49
	ds_read2_b32 v[48:49], v79 offset0:140 offset1:173
	s_waitcnt lgkmcnt(0)
	v_cvt_pk_bf16_f32 v48, v48, v49
	ds_read2_b32 v[52:53], v79 offset0:206 offset1:239
	s_waitcnt lgkmcnt(0)
	v_cvt_pk_bf16_f32 v49, v52, v53
	global_store_dwordx4 v[56:57], v[46:49], off
	ds_read2_b32 v[46:47], v79 offset0:16 offset1:49
	v_add_u32_e32 v50, 24, v50
	s_waitcnt lgkmcnt(0)
	v_cvt_pk_bf16_f32 v46, v46, v47
	ds_read2_b32 v[48:49], v79 offset0:82 offset1:115
	s_waitcnt lgkmcnt(0)
	v_cvt_pk_bf16_f32 v47, v48, v49
	ds_read2_b32 v[48:49], v79 offset0:148 offset1:181
	s_waitcnt lgkmcnt(0)
	v_cvt_pk_bf16_f32 v48, v48, v49
	ds_read2_b32 v[52:53], v79 offset0:214 offset1:247
	s_waitcnt lgkmcnt(0)
	v_cvt_pk_bf16_f32 v49, v52, v53
	global_store_dwordx4 v[54:55], v[46:49], off
	ds_read2_b32 v[46:47], v79 offset0:24 offset1:57
	v_ashrrev_i32_e32 v51, 31, v50
	s_waitcnt lgkmcnt(0)
	v_cvt_pk_bf16_f32 v46, v46, v47
	ds_read2_b32 v[48:49], v79 offset0:90 offset1:123
	v_lshlrev_b64 v[50:51], 11, v[50:51]
	s_waitcnt lgkmcnt(0)
	v_cvt_pk_bf16_f32 v47, v48, v49
	ds_read2_b32 v[48:49], v79 offset0:156 offset1:189
	v_lshl_add_u64 v[44:45], v[44:45], 0, v[50:51]
	s_waitcnt lgkmcnt(0)
	v_cvt_pk_bf16_f32 v48, v48, v49
	ds_read2_b32 v[52:53], v79 offset0:222 offset1:255
	s_waitcnt lgkmcnt(0)
	v_cvt_pk_bf16_f32 v49, v52, v53
	global_store_dwordx4 v[44:45], v[46:49], off
	s_waitcnt lgkmcnt(0)
	s_add_i32 s41, s41, s60
	s_add_i32 s7, s7, s8
	s_cmpk_gt_i32 s41, 0x1ff
	s_cbranch_scc0 .LBB0_17

; __device__ __forceinline__ void p0_transpose_item(const float* W, int K, int N, bf16_t* WT, LAS float* scr, int item, int lane) {
;     const int nblk = N / 32, kb = item / nblk, nb = item % nblk, k0 = 64 * kb, n0 = 32 * nb;
;     float tv[32];
; #pragma unroll
;     for (int i = 0; i < 32; ++i) tv[i] = W[(size_t)(k0 + 2 * i + (lane >> 5)) * N + n0 + (lane & 31)];
.LBB0_20:
	s_mul_hi_i32 s42, s41, 0x2aaaaaab
	s_lshr_b32 s43, s42, 31
	s_ashr_i32 s42, s42, 1
	s_add_i32 s42, s42, s43
	s_lshl_b32 s44, s42, 6
	s_mulk_i32 s42, 0xfe80
	s_add_i32 s42, s7, s42
	v_or_b32_e32 v2, s44, v5
	s_ashr_i32 s43, s42, 31
	v_or_b32_e32 v58, 12, v2
	v_or_b32_e32 v60, 14, v2
	v_or_b32_e32 v62, 16, v2
	v_or_b32_e32 v64, 18, v2
	v_or_b32_e32 v66, 20, v2
	v_or_b32_e32 v68, 22, v2
	v_or_b32_e32 v72, 24, v2
	v_or_b32_e32 v74, 26, v2
	v_or_b32_e32 v76, 28, v2
	v_or_b32_e32 v92, 30, v2
	v_or_b32_e32 v94, 32, v2
	v_or_b32_e32 v96, 34, v2
	v_or_b32_e32 v98, 36, v2
	v_lshl_add_u64 v[44:45], s[42:43], 2, v[40:41]
	v_or_b32_e32 v48, 2, v2
	v_or_b32_e32 v50, 4, v2
	v_or_b32_e32 v52, 6, v2
	v_or_b32_e32 v54, 8, v2
	v_or_b32_e32 v56, 10, v2
	v_or_b32_e32 v100, 38, v2
	v_or_b32_e32 v102, 40, v2
	v_or_b32_e32 v104, 42, v2
	v_or_b32_e32 v106, 44, v2
	v_or_b32_e32 v108, 46, v2
	v_or_b32_e32 v110, 48, v2
	v_or_b32_e32 v112, 50, v2
	v_or_b32_e32 v114, 52, v2
	v_or_b32_e32 v116, 54, v2
	v_or_b32_e32 v118, 56, v2
	v_or_b32_e32 v120, 58, v2
	v_or_b32_e32 v122, 60, v2
	v_or_b32_e32 v124, 62, v2
	v_mad_i64_i32 v[46:47], s[46:47], v2, s52, v[44:45]
	v_mad_i64_i32 v[58:59], s[46:47], v58, s52, v[44:45]
	v_mad_i64_i32 v[60:61], s[46:47], v60, s52, v[44:45]
	v_mad_i64_i32 v[62:63], s[46:47], v62, s52, v[44:45]
	v_mad_i64_i32 v[64:65], s[46:47], v64, s52, v[44:45]
	v_mad_i64_i32 v[66:67], s[46:47], v66, s52, v[44:45]
	v_mad_i64_i32 v[68:69], s[46:47], v68, s52, v[44:45]
	v_mad_i64_i32 v[72:73], s[46:47], v72, s52, v[44:45]
	v_mad_i64_i32 v[74:75], s[46:47], v74, s52, v[44:45]
	v_mad_i64_i32 v[76:77], s[46:47], v76, s52, v[44:45]
	v_mad_i64_i32 v[92:93], s[46:47], v92, s52, v[44:45]
	v_mad_i64_i32 v[94:95], s[46:47], v94, s52, v[44:45]
	v_mad_i64_i32 v[96:97], s[46:47], v96, s52, v[44:45]
	v_mad_i64_i32 v[98:99], s[46:47], v98, s52, v[44:45]
	v_mad_i64_i32 v[48:49], s[46:47], v48, s52, v[44:45]
	v_mad_i64_i32 v[50:51], s[46:47], v50, s52, v[44:45]
	v_mad_i64_i32 v[52:53], s[46:47], v52, s52, v[44:45]
	v_mad_i64_i32 v[54:55], s[46:47], v54, s52, v[44:45]
	v_mad_i64_i32 v[56:57], s[46:47], v56, s52, v[44:45]
	v_mad_i64_i32 v[100:101], s[46:47], v100, s52, v[44:45]
	v_mad_i64_i32 v[102:103], s[46:47], v102, s52, v[44:45]
	v_mad_i64_i32 v[104:105], s[46:47], v104, s52, v[44:45]
	v_mad_i64_i32 v[106:107], s[46:47], v106, s52, v[44:45]
	v_mad_i64_i32 v[108:109], s[46:47], v108, s52, v[44:45]
	v_mad_i64_i32 v[110:111], s[46:47], v110, s52, v[44:45]
	v_mad_i64_i32 v[112:113], s[46:47], v112, s52, v[44:45]
	v_mad_i64_i32 v[114:115], s[46:47], v114, s52, v[44:45]
	v_mad_i64_i32 v[116:117], s[46:47], v116, s52, v[44:45]
	v_mad_i64_i32 v[118:119], s[46:47], v118, s52, v[44:45]
	v_mad_i64_i32 v[120:121], s[46:47], v120, s52, v[44:45]
	v_mad_i64_i32 v[122:123], s[46:47], v122, s52, v[44:45]
	v_mad_i64_i32 v[44:45], s[46:47], v124, s52, v[44:45]
	global_load_dword v2, v[46:47], off
	global_load_dword v124, v[48:49], off
	global_load_dword v125, v[50:51], off
	global_load_dword v126, v[52:53], off
	global_load_dword v127, v[54:55], off
	global_load_dword v128, v[56:57], off
	s_nop 0
	global_load_dword v58, v[58:59], off
	s_nop 0
	global_load_dword v59, v[60:61], off
	s_nop 0
	global_load_dword v60, v[62:63], off
	global_load_dword v61, v[64:65], off
	s_nop 0
	global_load_dword v62, v[66:67], off
	global_load_dword v63, v[68:69], off
	global_load_dword v64, v[72:73], off
	global_load_dword v65, v[74:75], off
	s_nop 0
	global_load_dword v66, v[76:77], off
	global_load_dword v67, v[92:93], off
	global_load_dword v68, v[94:95], off
	global_load_dword v69, v[96:97], off
	global_load_dword v72, v[98:99], off
	global_load_dword v73, v[100:101], off
	global_load_dword v74, v[102:103], off
	global_load_dword v75, v[104:105], off
	global_load_dword v76, v[106:107], off
	global_load_dword v77, v[108:109], off
	global_load_dword v92, v[110:111], off
	global_load_dword v93, v[112:113], off
	global_load_dword v94, v[114:115], off
	global_load_dword v95, v[116:117], off
	global_load_dword v96, v[118:119], off
	global_load_dword v97, v[120:121], off
	global_load_dword v98, v[122:123], off
	global_load_dword v99, v[44:45], off
	v_add_u32_e32 v50, s42, v78
	v_add_u32_e32 v44, 8, v50
	s_ashr_i32 s45, s44, 31
	v_ashrrev_i32_e32 v45, 31, v44
	s_waitcnt vmcnt(0)
; #define LAS __attribute__((address_space(3)))
; __device__ __forceinline__ unsigned cvt_pk_bf16(float lo, float hi) { unsigned r; asm volatile("v_cvt_pk_bf16_f32 %0, %1, %2" : "=v"(r) : "v"(lo), "v"(hi)); return r; }
; __device__ __forceinline__ void p0_transpose_item(const float* W, int K, int N, bf16_t* WT, LAS float* scr, int item, int lane) {
;     ...
; #pragma unroll
;     for (int i = 0; i < 32; ++i) scr[(2 * i + (lane >> 5)) * 33 + (lane & 31)] = tv[i];
;     asm volatile("s_waitcnt lgkmcnt(0)" ::: "memory");
;     const int c = lane & 7;
; #pragma unroll
;     for (int j = 0; j < 4; ++j) { const int n = (lane >> 3) + 8 * j; const LAS float* s = scr + (8 * c) * 33 + n;
;         u32x4 o; o.x = cvt_pk_bf16(s[0 * 33], s[1 * 33]); o.y = cvt_pk_bf16(s[2 * 33], s[3 * 33]); o.z = cvt_pk_bf16(s[4 * 33], s[5 * 33]); o.w = cvt_pk_bf16(s[6 * 33], s[7 * 33]);
;         *(u32x4*)(WT + (size_t)(n0 + n) * K + k0 + 8 * c) = o; }
;     asm volatile("s_waitcnt lgkmcnt(0)" ::: "memory");
	ds_write2_b32 v71, v2, v124 offset1:66
	ds_write2_b32 v71, v125, v126 offset0:132 offset1:198
	ds_write2_b32 v81, v127, v128 offset0:8 offset1:74
	ds_write2_b32 v81, v58, v59 offset0:140 offset1:206
	ds_write2_b32 v82, v60, v61 offset0:16 offset1:82
	ds_write2_b32 v82, v62, v63 offset0:148 offset1:214
	ds_write2_b32 v83, v64, v65 offset0:24 offset1:90
	ds_write2_b32 v83, v66, v67 offset0:156 offset1:222
	ds_write2_b32 v84, v68, v69 offset0:32 offset1:98
	ds_write2_b32 v84, v72, v73 offset0:164 offset1:230
	ds_write2_b32 v85, v74, v75 offset0:40 offset1:106
	ds_write2_b32 v85, v76, v77 offset0:172 offset1:238
	ds_write2_b32 v86, v92, v93 offset0:48 offset1:114
	ds_write2_b32 v86, v94, v95 offset0:180 offset1:246
	ds_write2_b32 v87, v96, v97 offset0:56 offset1:122
	ds_write2_b32 v87, v98, v99 offset0:188 offset1:254
	v_lshl_add_u64 v[48:49], s[44:45], 1, v[42:43]
	v_add_u32_e32 v46, 16, v50
	v_lshlrev_b64 v[44:45], 9, v[44:45]
	s_waitcnt lgkmcnt(0)
	v_ashrrev_i32_e32 v51, 31, v50
	v_ashrrev_i32_e32 v47, 31, v46
	v_lshl_add_u64 v[56:57], v[48:49], 0, v[44:45]
	ds_read2_b32 v[44:45], v79 offset1:33
	v_lshlrev_b64 v[52:53], 9, v[50:51]
	v_lshlrev_b64 v[54:55], 9, v[46:47]
	s_waitcnt lgkmcnt(0)
	v_cvt_pk_bf16_f32 v44, v44, v45
	ds_read2_b32 v[46:47], v79 offset0:66 offset1:99
	v_lshl_add_u64 v[52:53], v[48:49], 0, v[52:53]
	s_waitcnt lgkmcnt(0)
	v_cvt_pk_bf16_f32 v45, v46, v47
	ds_read2_b32 v[46:47], v79 offset0:132 offset1:165
	s_waitcnt lgkmcnt(0)
	v_cvt_pk_bf16_f32 v46, v46, v47
	ds_read2_b32 v[58:59], v79 offset0:198 offset1:231
	s_waitcnt lgkmcnt(0)
	v_cvt_pk_bf16_f32 v47, v58, v59
	global_store_dwordx4 v[52:53], v[44:47], off
	ds_read2_b32 v[44:45], v79 offset0:8 offset1:41
	v_lshl_add_u64 v[54:55], v[48:49], 0, v[54:55]
	s_waitcnt lgkmcnt(0)
	v_cvt_pk_bf16_f32 v44, v44, v45
	ds_read2_b32 v[46:47], v79 offset0:74 offset1:107
	s_waitcnt lgkmcnt(0)
	v_cvt_pk_bf16_f32 v45, v46, v47
	ds_read2_b32 v[46:47], v79 offset0:140 offset1:173
	s_waitcnt lgkmcnt(0)
	v_cvt_pk_bf16_f32 v46, v46, v47
	ds_read2_b32 v[52:53], v79 offset0:206 offset1:239
	s_waitcnt lgkmcnt(0)
	v_cvt_pk_bf16_f32 v47, v52, v53
	global_store_dwordx4 v[56:57], v[44:47], off
	ds_read2_b32 v[44:45], v79 offset0:16 offset1:49
	v_add_u32_e32 v50, 24, v50
	s_waitcnt lgkmcnt(0)
	v_cvt_pk_bf16_f32 v44, v44, v45
	ds_read2_b32 v[46:47], v79 offset0:82 offset1:115
	s_waitcnt lgkmcnt(0)
	v_cvt_pk_bf16_f32 v45, v46, v47
	ds_read2_b32 v[46:47], v79 offset0:148 offset1:181
	s_waitcnt lgkmcnt(0)
	v_cvt_pk_bf16_f32 v46, v46, v47
	ds_read2_b32 v[52:53], v79 offset0:214 offset1:247
	s_waitcnt lgkmcnt(0)
	v_cvt_pk_bf16_f32 v47, v52, v53
	global_store_dwordx4 v[54:55], v[44:47], off
	ds_read2_b32 v[44:45], v79 offset0:24 offset1:57
	v_ashrrev_i32_e32 v51, 31, v50
	s_waitcnt lgkmcnt(0)
	v_cvt_pk_bf16_f32 v44, v44, v45
	ds_read2_b32 v[46:47], v79 offset0:90 offset1:123
	v_lshlrev_b64 v[50:51], 9, v[50:51]
	s_waitcnt lgkmcnt(0)
	v_cvt_pk_bf16_f32 v45, v46, v47
	ds_read2_b32 v[46:47], v79 offset0:156 offset1:189
	v_lshl_add_u64 v[48:49], v[48:49], 0, v[50:51]
	s_waitcnt lgkmcnt(0)
	v_cvt_pk_bf16_f32 v46, v46, v47
	ds_read2_b32 v[52:53], v79 offset0:222 offset1:255
	s_waitcnt lgkmcnt(0)
	v_cvt_pk_bf16_f32 v47, v52, v53
	global_store_dwordx4 v[48:49], v[44:47], off
	s_waitcnt lgkmcnt(0)
	s_add_i32 s41, s41, s60
	s_add_i32 s7, s7, s8
	s_cmp_gt_i32 s41, 47
	s_cbranch_scc0 .LBB0_20

; __device__ __forceinline__ void p0_transpose_item(const float* W, int K, int N, bf16_t* WT, LAS float* scr, int item, int lane) {
;     const int nblk = N / 32, kb = item / nblk, nb = item % nblk, k0 = 64 * kb, n0 = 32 * nb;
;     float tv[32];
; #pragma unroll
;     for (int i = 0; i < 32; ++i) tv[i] = W[(size_t)(k0 + 2 * i + (lane >> 5)) * N + n0 + (lane & 31)];
.LBB0_23:
	s_ashr_i32 s42, s46, 31
	s_lshr_b32 s42, s42, 28
	s_add_i32 s42, s46, s42
	s_ashr_i32 s42, s42, 4
	s_lshl_b32 s44, s42, 6
	s_lshl_b32 s42, s42, 9
	v_or_b32_e32 v54, s44, v5
	s_sub_i32 s42, s8, s42
	v_or_b32_e32 v58, 14, v54
	v_or_b32_e32 v60, 16, v54
	v_or_b32_e32 v62, 18, v54
	v_or_b32_e32 v64, 20, v54
	v_or_b32_e32 v66, 22, v54
	v_or_b32_e32 v68, 24, v54
	v_or_b32_e32 v72, 26, v54
	v_or_b32_e32 v74, 28, v54
	v_or_b32_e32 v76, 30, v54
	v_or_b32_e32 v92, 32, v54
	v_or_b32_e32 v94, 34, v54
	v_or_b32_e32 v96, 36, v54
	v_or_b32_e32 v98, 38, v54
	s_ashr_i32 s43, s42, 31
	v_ashrrev_i32_e32 v55, 31, v54
	v_or_b32_e32 v44, 2, v54
	v_or_b32_e32 v46, 4, v54
	v_or_b32_e32 v48, 6, v54
	v_or_b32_e32 v50, 8, v54
	v_or_b32_e32 v52, 10, v54
	v_or_b32_e32 v56, 12, v54
	v_or_b32_e32 v100, 40, v54
	v_or_b32_e32 v102, 42, v54
	v_or_b32_e32 v104, 44, v54
	v_or_b32_e32 v106, 46, v54
	v_or_b32_e32 v108, 48, v54
	v_or_b32_e32 v110, 50, v54
	v_or_b32_e32 v112, 52, v54
	v_or_b32_e32 v114, 54, v54
	v_or_b32_e32 v116, 56, v54
	v_or_b32_e32 v118, 58, v54
	v_or_b32_e32 v120, 60, v54
	v_or_b32_e32 v122, 62, v54
	v_ashrrev_i32_e32 v59, 31, v58
	v_ashrrev_i32_e32 v61, 31, v60
	v_ashrrev_i32_e32 v63, 31, v62
	v_ashrrev_i32_e32 v65, 31, v64
	v_ashrrev_i32_e32 v67, 31, v66
	v_ashrrev_i32_e32 v69, 31, v68
	v_ashrrev_i32_e32 v73, 31, v72
	v_ashrrev_i32_e32 v75, 31, v74
	v_ashrrev_i32_e32 v77, 31, v76
	v_ashrrev_i32_e32 v93, 31, v92
	v_ashrrev_i32_e32 v95, 31, v94
	v_ashrrev_i32_e32 v97, 31, v96
	v_ashrrev_i32_e32 v99, 31, v98
	v_lshl_add_u64 v[124:125], s[42:43], 2, v[40:41]
	v_lshlrev_b64 v[54:55], 11, v[54:55]
	v_ashrrev_i32_e32 v45, 31, v44
	v_ashrrev_i32_e32 v47, 31, v46
	v_ashrrev_i32_e32 v49, 31, v48
	v_ashrrev_i32_e32 v51, 31, v50
	v_ashrrev_i32_e32 v53, 31, v52
	v_ashrrev_i32_e32 v57, 31, v56
	v_ashrrev_i32_e32 v101, 31, v100
	v_ashrrev_i32_e32 v103, 31, v102
	v_ashrrev_i32_e32 v105, 31, v104
	v_ashrrev_i32_e32 v107, 31, v106
	v_ashrrev_i32_e32 v109, 31, v108
	v_ashrrev_i32_e32 v111, 31, v110
	v_ashrrev_i32_e32 v113, 31, v112
	v_ashrrev_i32_e32 v115, 31, v114
	v_ashrrev_i32_e32 v117, 31, v116
	v_ashrrev_i32_e32 v119, 31, v118
	v_ashrrev_i32_e32 v121, 31, v120
	v_ashrrev_i32_e32 v123, 31, v122
	v_lshlrev_b64 v[58:59], 11, v[58:59]
	v_lshlrev_b64 v[60:61], 11, v[60:61]
	v_lshlrev_b64 v[62:63], 11, v[62:63]
	v_lshlrev_b64 v[64:65], 11, v[64:65]
	v_lshlrev_b64 v[66:67], 11, v[66:67]
	v_lshlrev_b64 v[68:69], 11, v[68:69]
	v_lshlrev_b64 v[72:73], 11, v[72:73]
	v_lshlrev_b64 v[74:75], 11, v[74:75]
	v_lshlrev_b64 v[76:77], 11, v[76:77]
	v_lshlrev_b64 v[92:93], 11, v[92:93]
	v_lshlrev_b64 v[94:95], 11, v[94:95]
	v_lshlrev_b64 v[96:97], 11, v[96:97]
	v_lshlrev_b64 v[98:99], 11, v[98:99]
	v_lshl_add_u64 v[54:55], v[124:125], 0, v[54:55]
	v_lshlrev_b64 v[44:45], 11, v[44:45]
	v_lshlrev_b64 v[46:47], 11, v[46:47]
	v_lshlrev_b64 v[48:49], 11, v[48:49]
	v_lshlrev_b64 v[50:51], 11, v[50:51]
	v_lshlrev_b64 v[52:53], 11, v[52:53]
	v_lshlrev_b64 v[56:57], 11, v[56:57]
	v_lshlrev_b64 v[100:101], 11, v[100:101]
	v_lshlrev_b64 v[102:103], 11, v[102:103]
	v_lshlrev_b64 v[104:105], 11, v[104:105]
	v_lshlrev_b64 v[106:107], 11, v[106:107]
	v_lshlrev_b64 v[108:109], 11, v[108:109]
	v_lshlrev_b64 v[110:111], 11, v[110:111]
	v_lshlrev_b64 v[112:113], 11, v[112:113]
	v_lshlrev_b64 v[114:115], 11, v[114:115]
	v_lshlrev_b64 v[116:117], 11, v[116:117]
	v_lshlrev_b64 v[118:119], 11, v[118:119]
	v_lshlrev_b64 v[120:121], 11, v[120:121]
	v_lshlrev_b64 v[122:123], 11, v[122:123]
	v_lshl_add_u64 v[58:59], v[124:125], 0, v[58:59]
	v_lshl_add_u64 v[60:61], v[124:125], 0, v[60:61]
	v_lshl_add_u64 v[62:63], v[124:125], 0, v[62:63]
	v_lshl_add_u64 v[64:65], v[124:125], 0, v[64:65]
	v_lshl_add_u64 v[66:67], v[124:125], 0, v[66:67]
	v_lshl_add_u64 v[68:69], v[124:125], 0, v[68:69]
	v_lshl_add_u64 v[72:73], v[124:125], 0, v[72:73]
	v_lshl_add_u64 v[74:75], v[124:125], 0, v[74:75]
	v_lshl_add_u64 v[76:77], v[124:125], 0, v[76:77]
	v_lshl_add_u64 v[92:93], v[124:125], 0, v[92:93]
	v_lshl_add_u64 v[94:95], v[124:125], 0, v[94:95]
	v_lshl_add_u64 v[96:97], v[124:125], 0, v[96:97]
	v_lshl_add_u64 v[98:99], v[124:125], 0, v[98:99]
	v_lshl_add_u64 v[44:45], v[124:125], 0, v[44:45]
	v_lshl_add_u64 v[46:47], v[124:125], 0, v[46:47]
	v_lshl_add_u64 v[48:49], v[124:125], 0, v[48:49]
	v_lshl_add_u64 v[50:51], v[124:125], 0, v[50:51]
	v_lshl_add_u64 v[52:53], v[124:125], 0, v[52:53]
	v_lshl_add_u64 v[56:57], v[124:125], 0, v[56:57]
	v_lshl_add_u64 v[100:101], v[124:125], 0, v[100:101]
	v_lshl_add_u64 v[102:103], v[124:125], 0, v[102:103]
	v_lshl_add_u64 v[104:105], v[124:125], 0, v[104:105]
	v_lshl_add_u64 v[106:107], v[124:125], 0, v[106:107]
	v_lshl_add_u64 v[108:109], v[124:125], 0, v[108:109]
	v_lshl_add_u64 v[110:111], v[124:125], 0, v[110:111]
	v_lshl_add_u64 v[112:113], v[124:125], 0, v[112:113]
	v_lshl_add_u64 v[114:115], v[124:125], 0, v[114:115]
	v_lshl_add_u64 v[116:117], v[124:125], 0, v[116:117]
	v_lshl_add_u64 v[118:119], v[124:125], 0, v[118:119]
	v_lshl_add_u64 v[120:121], v[124:125], 0, v[120:121]
	v_lshl_add_u64 v[122:123], v[124:125], 0, v[122:123]
	global_load_dword v2, v[54:55], off
	global_load_dword v124, v[44:45], off
	global_load_dword v125, v[46:47], off
	global_load_dword v126, v[48:49], off
	global_load_dword v127, v[50:51], off
	global_load_dword v128, v[52:53], off
	global_load_dword v129, v[56:57], off
	s_nop 0
	global_load_dword v58, v[58:59], off
	s_nop 0
	global_load_dword v59, v[60:61], off
	s_nop 0
	global_load_dword v60, v[62:63], off
	global_load_dword v61, v[64:65], off
	s_nop 0
	global_load_dword v62, v[66:67], off
	global_load_dword v63, v[68:69], off
	global_load_dword v64, v[72:73], off
	global_load_dword v65, v[74:75], off
	s_nop 0
	global_load_dword v66, v[76:77], off
	global_load_dword v67, v[92:93], off
	global_load_dword v68, v[94:95], off
	global_load_dword v69, v[96:97], off
	global_load_dword v72, v[98:99], off
	global_load_dword v73, v[100:101], off
	global_load_dword v74, v[102:103], off
	global_load_dword v75, v[104:105], off
	global_load_dword v76, v[106:107], off
	global_load_dword v77, v[108:109], off
	global_load_dword v92, v[110:111], off
	global_load_dword v93, v[112:113], off
	global_load_dword v94, v[114:115], off
	global_load_dword v95, v[116:117], off
	global_load_dword v96, v[118:119], off
	global_load_dword v97, v[120:121], off
	global_load_dword v98, v[122:123], off
	v_add_u32_e32 v50, s42, v78
	v_add_u32_e32 v46, 8, v50
	s_ashr_i32 s45, s44, 31
	v_ashrrev_i32_e32 v47, 31, v46
	s_waitcnt vmcnt(0)
; #define LAS __attribute__((address_space(3)))
; __device__ __forceinline__ unsigned cvt_pk_bf16(float lo, float hi) { unsigned r; asm volatile("v_cvt_pk_bf16_f32 %0, %1, %2" : "=v"(r) : "v"(lo), "v"(hi)); return r; }
; __device__ __forceinline__ void p0_transpose_item(const float* W, int K, int N, bf16_t* WT, LAS float* scr, int item, int lane) {
;     ...
; #pragma unroll
;     for (int i = 0; i < 32; ++i) scr[(2 * i + (lane >> 5)) * 33 + (lane & 31)] = tv[i];
;     asm volatile("s_waitcnt lgkmcnt(0)" ::: "memory");
;     const int c = lane & 7;
; #pragma unroll
;     for (int j = 0; j < 4; ++j) { const int n = (lane >> 3) + 8 * j; const LAS float* s = scr + (8 * c) * 33 + n;
;         u32x4 o; o.x = cvt_pk_bf16(s[0 * 33], s[1 * 33]); o.y = cvt_pk_bf16(s[2 * 33], s[3 * 33]); o.z = cvt_pk_bf16(s[4 * 33], s[5 * 33]); o.w = cvt_pk_bf16(s[6 * 33], s[7 * 33]);
;         *(u32x4*)(WT + (size_t)(n0 + n) * K + k0 + 8 * c) = o; }
;     asm volatile("s_waitcnt lgkmcnt(0)" ::: "memory");
	ds_write2_b32 v71, v2, v124 offset1:66
	ds_write2_b32 v71, v125, v126 offset0:132 offset1:198
	ds_write2_b32 v81, v127, v128 offset0:8 offset1:74
	ds_write2_b32 v81, v129, v58 offset0:140 offset1:206
	ds_write2_b32 v82, v59, v60 offset0:16 offset1:82
	ds_write2_b32 v82, v61, v62 offset0:148 offset1:214
	ds_write2_b32 v83, v63, v64 offset0:24 offset1:90
	ds_write2_b32 v83, v65, v66 offset0:156 offset1:222
	ds_write2_b32 v84, v67, v68 offset0:32 offset1:98
	ds_write2_b32 v84, v69, v72 offset0:164 offset1:230
	ds_write2_b32 v85, v73, v74 offset0:40 offset1:106
	ds_write2_b32 v85, v75, v76 offset0:172 offset1:238
	ds_write2_b32 v86, v77, v92 offset0:48 offset1:114
	ds_write2_b32 v86, v93, v94 offset0:180 offset1:246
	ds_write2_b32 v87, v95, v96 offset0:56 offset1:122
	ds_write2_b32 v87, v97, v98 offset0:188 offset1:254
	v_lshl_add_u64 v[44:45], s[44:45], 1, v[42:43]
	v_add_u32_e32 v48, 16, v50
	v_lshlrev_b64 v[46:47], 8, v[46:47]
	s_waitcnt lgkmcnt(0)
	v_ashrrev_i32_e32 v51, 31, v50
	v_ashrrev_i32_e32 v49, 31, v48
	v_lshl_add_u64 v[56:57], v[44:45], 0, v[46:47]
	ds_read2_b32 v[46:47], v79 offset1:33
	v_lshlrev_b64 v[52:53], 8, v[50:51]
	v_lshlrev_b64 v[54:55], 8, v[48:49]
	s_waitcnt lgkmcnt(0)
	v_cvt_pk_bf16_f32 v46, v46, v47
	ds_read2_b32 v[48:49], v79 offset0:66 offset1:99
	v_lshl_add_u64 v[52:53], v[44:45], 0, v[52:53]
	s_waitcnt lgkmcnt(0)
	v_cvt_pk_bf16_f32 v47, v48, v49
	ds_read2_b32 v[48:49], v79 offset0:132 offset1:165
	s_waitcnt lgkmcnt(0)
	v_cvt_pk_bf16_f32 v48, v48, v49
	ds_read2_b32 v[58:59], v79 offset0:198 offset1:231
	s_waitcnt lgkmcnt(0)
	v_cvt_pk_bf16_f32 v49, v58, v59
	global_store_dwordx4 v[52:53], v[46:49], off
	ds_read2_b32 v[46:47], v79 offset0:8 offset1:41
	v_lshl_add_u64 v[54:55], v[44:45], 0, v[54:55]
	s_waitcnt lgkmcnt(0)
	v_cvt_pk_bf16_f32 v46, v46, v47
	ds_read2_b32 v[48:49], v79 offset0:74 offset1:107
	s_waitcnt lgkmcnt(0)
	v_cvt_pk_bf16_f32 v47, v48, v49
	ds_read2_b32 v[48:49], v79 offset0:140 offset1:173
	s_waitcnt lgkmcnt(0)
	v_cvt_pk_bf16_f32 v48, v48, v49
	ds_read2_b32 v[52:53], v79 offset0:206 offset1:239
	s_waitcnt lgkmcnt(0)
	v_cvt_pk_bf16_f32 v49, v52, v53
	global_store_dwordx4 v[56:57], v[46:49], off
	ds_read2_b32 v[46:47], v79 offset0:16 offset1:49
	v_add_u32_e32 v50, 24, v50
	s_waitcnt lgkmcnt(0)
	v_cvt_pk_bf16_f32 v46, v46, v47
	ds_read2_b32 v[48:49], v79 offset0:82 offset1:115
	s_waitcnt lgkmcnt(0)
	v_cvt_pk_bf16_f32 v47, v48, v49
	ds_read2_b32 v[48:49], v79 offset0:148 offset1:181
	s_waitcnt lgkmcnt(0)
	v_cvt_pk_bf16_f32 v48, v48, v49
	ds_read2_b32 v[52:53], v79 offset0:214 offset1:247
	s_waitcnt lgkmcnt(0)
	v_cvt_pk_bf16_f32 v49, v52, v53
	global_store_dwordx4 v[54:55], v[46:49], off
	ds_read2_b32 v[46:47], v79 offset0:24 offset1:57
	v_ashrrev_i32_e32 v51, 31, v50
	s_waitcnt lgkmcnt(0)
	v_cvt_pk_bf16_f32 v46, v46, v47
	ds_read2_b32 v[48:49], v79 offset0:90 offset1:123
	v_lshlrev_b64 v[50:51], 8, v[50:51]
	s_waitcnt lgkmcnt(0)
	v_cvt_pk_bf16_f32 v47, v48, v49
	ds_read2_b32 v[48:49], v79 offset0:156 offset1:189
	v_lshl_add_u64 v[44:45], v[44:45], 0, v[50:51]
	s_waitcnt lgkmcnt(0)
	v_cvt_pk_bf16_f32 v48, v48, v49
	ds_read2_b32 v[52:53], v79 offset0:222 offset1:255
	s_waitcnt lgkmcnt(0)
	v_cvt_pk_bf16_f32 v49, v52, v53
	global_store_dwordx4 v[44:45], v[46:49], off
	s_waitcnt lgkmcnt(0)
	s_add_i32 s46, s46, s60
	s_add_i32 s8, s8, s41
	s_cmp_gt_i32 s46, 31
	s_cbranch_scc0 .LBB0_23

; __device__ __forceinline__ void p0_transpose_item(const float* W, int K, int N, bf16_t* WT, LAS float* scr, int item, int lane) {
;     const int nblk = N / 32, kb = item / nblk, nb = item % nblk, k0 = 64 * kb, n0 = 32 * nb;
;     float tv[32];
; #pragma unroll
;     for (int i = 0; i < 32; ++i) tv[i] = W[(size_t)(k0 + 2 * i + (lane >> 5)) * N + n0 + (lane & 31)];
.LBB0_25:
	s_ashr_i32 s42, s8, 31
	s_lshr_b32 s42, s42, 29
	s_add_i32 s42, s8, s42
	s_ashr_i32 s42, s42, 3
	s_lshl_b32 s44, s42, 6
	s_lshl_b32 s42, s42, 8
	v_or_b32_e32 v54, s44, v5
	s_sub_i32 s42, s7, s42
	v_or_b32_e32 v58, 14, v54
	v_or_b32_e32 v60, 16, v54
	v_or_b32_e32 v62, 18, v54
	v_or_b32_e32 v64, 20, v54
	v_or_b32_e32 v66, 22, v54
	v_or_b32_e32 v68, 24, v54
	v_or_b32_e32 v72, 26, v54
	v_or_b32_e32 v74, 28, v54
	v_or_b32_e32 v76, 30, v54
	v_or_b32_e32 v92, 32, v54
	v_or_b32_e32 v94, 34, v54
	v_or_b32_e32 v96, 36, v54
	v_or_b32_e32 v98, 38, v54
	s_ashr_i32 s43, s42, 31
	v_ashrrev_i32_e32 v55, 31, v54
	v_or_b32_e32 v44, 2, v54
	v_or_b32_e32 v46, 4, v54
	v_or_b32_e32 v48, 6, v54
	v_or_b32_e32 v50, 8, v54
	v_or_b32_e32 v52, 10, v54
	v_or_b32_e32 v56, 12, v54
	v_or_b32_e32 v100, 40, v54
	v_or_b32_e32 v102, 42, v54
	v_or_b32_e32 v104, 44, v54
	v_or_b32_e32 v106, 46, v54
	v_or_b32_e32 v108, 48, v54
	v_or_b32_e32 v110, 50, v54
	v_or_b32_e32 v112, 52, v54
	v_or_b32_e32 v114, 54, v54
	v_or_b32_e32 v116, 56, v54
	v_or_b32_e32 v118, 58, v54
	v_or_b32_e32 v120, 60, v54
	v_or_b32_e32 v122, 62, v54
	v_ashrrev_i32_e32 v59, 31, v58
	v_ashrrev_i32_e32 v61, 31, v60
	v_ashrrev_i32_e32 v63, 31, v62
	v_ashrrev_i32_e32 v65, 31, v64
	v_ashrrev_i32_e32 v67, 31, v66
	v_ashrrev_i32_e32 v69, 31, v68
	v_ashrrev_i32_e32 v73, 31, v72
	v_ashrrev_i32_e32 v75, 31, v74
	v_ashrrev_i32_e32 v77, 31, v76
	v_ashrrev_i32_e32 v93, 31, v92
	v_ashrrev_i32_e32 v95, 31, v94
	v_ashrrev_i32_e32 v97, 31, v96
	v_ashrrev_i32_e32 v99, 31, v98
	v_lshl_add_u64 v[124:125], s[42:43], 2, v[40:41]
	v_lshlrev_b64 v[54:55], 10, v[54:55]
	v_ashrrev_i32_e32 v45, 31, v44
	v_ashrrev_i32_e32 v47, 31, v46
	v_ashrrev_i32_e32 v49, 31, v48
	v_ashrrev_i32_e32 v51, 31, v50
	v_ashrrev_i32_e32 v53, 31, v52
	v_ashrrev_i32_e32 v57, 31, v56
	v_ashrrev_i32_e32 v101, 31, v100
	v_ashrrev_i32_e32 v103, 31, v102
	v_ashrrev_i32_e32 v105, 31, v104
	v_ashrrev_i32_e32 v107, 31, v106
	v_ashrrev_i32_e32 v109, 31, v108
	v_ashrrev_i32_e32 v111, 31, v110
	v_ashrrev_i32_e32 v113, 31, v112
	v_ashrrev_i32_e32 v115, 31, v114
	v_ashrrev_i32_e32 v117, 31, v116
	v_ashrrev_i32_e32 v119, 31, v118
	v_ashrrev_i32_e32 v121, 31, v120
	v_ashrrev_i32_e32 v123, 31, v122
	v_lshlrev_b64 v[58:59], 10, v[58:59]
	v_lshlrev_b64 v[60:61], 10, v[60:61]
	v_lshlrev_b64 v[62:63], 10, v[62:63]
	v_lshlrev_b64 v[64:65], 10, v[64:65]
	v_lshlrev_b64 v[66:67], 10, v[66:67]
	v_lshlrev_b64 v[68:69], 10, v[68:69]
	v_lshlrev_b64 v[72:73], 10, v[72:73]
	v_lshlrev_b64 v[74:75], 10, v[74:75]
	v_lshlrev_b64 v[76:77], 10, v[76:77]
	v_lshlrev_b64 v[92:93], 10, v[92:93]
	v_lshlrev_b64 v[94:95], 10, v[94:95]
	v_lshlrev_b64 v[96:97], 10, v[96:97]
	v_lshlrev_b64 v[98:99], 10, v[98:99]
	v_lshl_add_u64 v[54:55], v[124:125], 0, v[54:55]
	v_lshlrev_b64 v[44:45], 10, v[44:45]
	v_lshlrev_b64 v[46:47], 10, v[46:47]
	v_lshlrev_b64 v[48:49], 10, v[48:49]
	v_lshlrev_b64 v[50:51], 10, v[50:51]
	v_lshlrev_b64 v[52:53], 10, v[52:53]
	v_lshlrev_b64 v[56:57], 10, v[56:57]
	v_lshlrev_b64 v[100:101], 10, v[100:101]
	v_lshlrev_b64 v[102:103], 10, v[102:103]
	v_lshlrev_b64 v[104:105], 10, v[104:105]
	v_lshlrev_b64 v[106:107], 10, v[106:107]
	v_lshlrev_b64 v[108:109], 10, v[108:109]
	v_lshlrev_b64 v[110:111], 10, v[110:111]
	v_lshlrev_b64 v[112:113], 10, v[112:113]
	v_lshlrev_b64 v[114:115], 10, v[114:115]
	v_lshlrev_b64 v[116:117], 10, v[116:117]
	v_lshlrev_b64 v[118:119], 10, v[118:119]
	v_lshlrev_b64 v[120:121], 10, v[120:121]
	v_lshlrev_b64 v[122:123], 10, v[122:123]
	v_lshl_add_u64 v[58:59], v[124:125], 0, v[58:59]
	v_lshl_add_u64 v[60:61], v[124:125], 0, v[60:61]
	v_lshl_add_u64 v[62:63], v[124:125], 0, v[62:63]
	v_lshl_add_u64 v[64:65], v[124:125], 0, v[64:65]
	v_lshl_add_u64 v[66:67], v[124:125], 0, v[66:67]
	v_lshl_add_u64 v[68:69], v[124:125], 0, v[68:69]
	v_lshl_add_u64 v[72:73], v[124:125], 0, v[72:73]
	v_lshl_add_u64 v[74:75], v[124:125], 0, v[74:75]
	v_lshl_add_u64 v[76:77], v[124:125], 0, v[76:77]
	v_lshl_add_u64 v[92:93], v[124:125], 0, v[92:93]
	v_lshl_add_u64 v[94:95], v[124:125], 0, v[94:95]
	v_lshl_add_u64 v[96:97], v[124:125], 0, v[96:97]
	v_lshl_add_u64 v[98:99], v[124:125], 0, v[98:99]
	v_lshl_add_u64 v[44:45], v[124:125], 0, v[44:45]
	v_lshl_add_u64 v[46:47], v[124:125], 0, v[46:47]
	v_lshl_add_u64 v[48:49], v[124:125], 0, v[48:49]
	v_lshl_add_u64 v[50:51], v[124:125], 0, v[50:51]
	v_lshl_add_u64 v[52:53], v[124:125], 0, v[52:53]
	v_lshl_add_u64 v[56:57], v[124:125], 0, v[56:57]
	v_lshl_add_u64 v[100:101], v[124:125], 0, v[100:101]
	v_lshl_add_u64 v[102:103], v[124:125], 0, v[102:103]
	v_lshl_add_u64 v[104:105], v[124:125], 0, v[104:105]
	v_lshl_add_u64 v[106:107], v[124:125], 0, v[106:107]
	v_lshl_add_u64 v[108:109], v[124:125], 0, v[108:109]
	v_lshl_add_u64 v[110:111], v[124:125], 0, v[110:111]
	v_lshl_add_u64 v[112:113], v[124:125], 0, v[112:113]
	v_lshl_add_u64 v[114:115], v[124:125], 0, v[114:115]
	v_lshl_add_u64 v[116:117], v[124:125], 0, v[116:117]
	v_lshl_add_u64 v[118:119], v[124:125], 0, v[118:119]
	v_lshl_add_u64 v[120:121], v[124:125], 0, v[120:121]
	v_lshl_add_u64 v[122:123], v[124:125], 0, v[122:123]
	global_load_dword v2, v[54:55], off
	global_load_dword v124, v[44:45], off
	global_load_dword v125, v[46:47], off
	global_load_dword v126, v[48:49], off
	global_load_dword v127, v[50:51], off
	global_load_dword v128, v[52:53], off
	global_load_dword v129, v[56:57], off
	s_nop 0
	global_load_dword v58, v[58:59], off
	s_nop 0
	global_load_dword v59, v[60:61], off
	s_nop 0
	global_load_dword v60, v[62:63], off
	global_load_dword v61, v[64:65], off
	s_nop 0
	global_load_dword v62, v[66:67], off
	global_load_dword v63, v[68:69], off
	global_load_dword v64, v[72:73], off
	global_load_dword v65, v[74:75], off
	s_nop 0
	global_load_dword v66, v[76:77], off
	global_load_dword v67, v[92:93], off
	global_load_dword v68, v[94:95], off
	global_load_dword v69, v[96:97], off
	global_load_dword v72, v[98:99], off
	global_load_dword v73, v[100:101], off
	global_load_dword v74, v[102:103], off
	global_load_dword v75, v[104:105], off
	global_load_dword v76, v[106:107], off
	global_load_dword v77, v[108:109], off
	global_load_dword v92, v[110:111], off
	global_load_dword v93, v[112:113], off
	global_load_dword v94, v[114:115], off
	global_load_dword v95, v[116:117], off
	global_load_dword v96, v[118:119], off
	global_load_dword v97, v[120:121], off
	global_load_dword v98, v[122:123], off
	v_add_u32_e32 v50, s42, v78
	v_add_u32_e32 v46, 8, v50
	s_ashr_i32 s45, s44, 31
	v_ashrrev_i32_e32 v47, 31, v46
	s_waitcnt vmcnt(0)
; #define LAS __attribute__((address_space(3)))
; __device__ __forceinline__ unsigned cvt_pk_bf16(float lo, float hi) { unsigned r; asm volatile("v_cvt_pk_bf16_f32 %0, %1, %2" : "=v"(r) : "v"(lo), "v"(hi)); return r; }
; __device__ __forceinline__ void p0_transpose_item(const float* W, int K, int N, bf16_t* WT, LAS float* scr, int item, int lane) {
;     ...
; #pragma unroll
;     for (int i = 0; i < 32; ++i) scr[(2 * i + (lane >> 5)) * 33 + (lane & 31)] = tv[i];
;     asm volatile("s_waitcnt lgkmcnt(0)" ::: "memory");
;     const int c = lane & 7;
; #pragma unroll
;     for (int j = 0; j < 4; ++j) { const int n = (lane >> 3) + 8 * j; const LAS float* s = scr + (8 * c) * 33 + n;
;         u32x4 o; o.x = cvt_pk_bf16(s[0 * 33], s[1 * 33]); o.y = cvt_pk_bf16(s[2 * 33], s[3 * 33]); o.z = cvt_pk_bf16(s[4 * 33], s[5 * 33]); o.w = cvt_pk_bf16(s[6 * 33], s[7 * 33]);
;         *(u32x4*)(WT + (size_t)(n0 + n) * K + k0 + 8 * c) = o; }
;     asm volatile("s_waitcnt lgkmcnt(0)" ::: "memory");
	ds_write2_b32 v71, v2, v124 offset1:66
	ds_write2_b32 v71, v125, v126 offset0:132 offset1:198
	ds_write2_b32 v81, v127, v128 offset0:8 offset1:74
	ds_write2_b32 v81, v129, v58 offset0:140 offset1:206
	ds_write2_b32 v82, v59, v60 offset0:16 offset1:82
	ds_write2_b32 v82, v61, v62 offset0:148 offset1:214
	ds_write2_b32 v83, v63, v64 offset0:24 offset1:90
	ds_write2_b32 v83, v65, v66 offset0:156 offset1:222
	ds_write2_b32 v84, v67, v68 offset0:32 offset1:98
	ds_write2_b32 v84, v69, v72 offset0:164 offset1:230
	ds_write2_b32 v85, v73, v74 offset0:40 offset1:106
	ds_write2_b32 v85, v75, v76 offset0:172 offset1:238
	ds_write2_b32 v86, v77, v92 offset0:48 offset1:114
	ds_write2_b32 v86, v93, v94 offset0:180 offset1:246
	ds_write2_b32 v87, v95, v96 offset0:56 offset1:122
	ds_write2_b32 v87, v97, v98 offset0:188 offset1:254
	v_lshl_add_u64 v[44:45], s[44:45], 1, v[42:43]
	v_add_u32_e32 v48, 16, v50
	v_lshlrev_b64 v[46:47], 9, v[46:47]
	s_waitcnt lgkmcnt(0)
	v_ashrrev_i32_e32 v51, 31, v50
	v_ashrrev_i32_e32 v49, 31, v48
	v_lshl_add_u64 v[56:57], v[44:45], 0, v[46:47]
	ds_read2_b32 v[46:47], v79 offset1:33
	v_lshlrev_b64 v[52:53], 9, v[50:51]
	v_lshlrev_b64 v[54:55], 9, v[48:49]
	s_waitcnt lgkmcnt(0)
	v_cvt_pk_bf16_f32 v46, v46, v47
	ds_read2_b32 v[48:49], v79 offset0:66 offset1:99
	v_lshl_add_u64 v[52:53], v[44:45], 0, v[52:53]
	s_waitcnt lgkmcnt(0)
	v_cvt_pk_bf16_f32 v47, v48, v49
	ds_read2_b32 v[48:49], v79 offset0:132 offset1:165
	s_waitcnt lgkmcnt(0)
	v_cvt_pk_bf16_f32 v48, v48, v49
	ds_read2_b32 v[58:59], v79 offset0:198 offset1:231
	s_waitcnt lgkmcnt(0)
	v_cvt_pk_bf16_f32 v49, v58, v59
	global_store_dwordx4 v[52:53], v[46:49], off
	ds_read2_b32 v[46:47], v79 offset0:8 offset1:41
	v_lshl_add_u64 v[54:55], v[44:45], 0, v[54:55]
	s_waitcnt lgkmcnt(0)
	v_cvt_pk_bf16_f32 v46, v46, v47
	ds_read2_b32 v[48:49], v79 offset0:74 offset1:107
	s_waitcnt lgkmcnt(0)
	v_cvt_pk_bf16_f32 v47, v48, v49
	ds_read2_b32 v[48:49], v79 offset0:140 offset1:173
	s_waitcnt lgkmcnt(0)
	v_cvt_pk_bf16_f32 v48, v48, v49
	ds_read2_b32 v[52:53], v79 offset0:206 offset1:239
	s_waitcnt lgkmcnt(0)
	v_cvt_pk_bf16_f32 v49, v52, v53
	global_store_dwordx4 v[56:57], v[46:49], off
	ds_read2_b32 v[46:47], v79 offset0:16 offset1:49
	v_add_u32_e32 v50, 24, v50
	s_waitcnt lgkmcnt(0)
	v_cvt_pk_bf16_f32 v46, v46, v47
	ds_read2_b32 v[48:49], v79 offset0:82 offset1:115
	s_waitcnt lgkmcnt(0)
	v_cvt_pk_bf16_f32 v47, v48, v49
	ds_read2_b32 v[48:49], v79 offset0:148 offset1:181
	s_waitcnt lgkmcnt(0)
	v_cvt_pk_bf16_f32 v48, v48, v49
	ds_read2_b32 v[52:53], v79 offset0:214 offset1:247
	s_waitcnt lgkmcnt(0)
	v_cvt_pk_bf16_f32 v49, v52, v53
	global_store_dwordx4 v[54:55], v[46:49], off
	ds_read2_b32 v[46:47], v79 offset0:24 offset1:57
	v_ashrrev_i32_e32 v51, 31, v50
	s_waitcnt lgkmcnt(0)
	v_cvt_pk_bf16_f32 v46, v46, v47
	ds_read2_b32 v[48:49], v79 offset0:90 offset1:123
	v_lshlrev_b64 v[50:51], 9, v[50:51]
	s_waitcnt lgkmcnt(0)
	v_cvt_pk_bf16_f32 v47, v48, v49
	ds_read2_b32 v[48:49], v79 offset0:156 offset1:189
	v_lshl_add_u64 v[44:45], v[44:45], 0, v[50:51]
	s_waitcnt lgkmcnt(0)
	v_cvt_pk_bf16_f32 v48, v48, v49
	ds_read2_b32 v[52:53], v79 offset0:222 offset1:255
	s_waitcnt lgkmcnt(0)
	v_cvt_pk_bf16_f32 v49, v52, v53
	global_store_dwordx4 v[44:45], v[46:49], off
	s_waitcnt lgkmcnt(0)
	s_add_i32 s8, s8, s60
	s_add_i32 s7, s7, s41
	s_cmp_gt_i32 s8, 31
	s_cbranch_scc0 .LBB0_25

; __device__ __forceinline__ void p0_transpose_item(const float* W, int K, int N, bf16_t* WT, LAS float* scr, int item, int lane) {
;     const int nblk = N / 32, kb = item / nblk, nb = item % nblk, k0 = 64 * kb, n0 = 32 * nb;
;     float tv[32];
; #pragma unroll
;     for (int i = 0; i < 32; ++i) tv[i] = W[(size_t)(k0 + 2 * i + (lane >> 5)) * N + n0 + (lane & 31)];
.LBB0_30:
	s_lshr_b32 s44, s58, 31
	s_add_i32 s44, s58, s44
	s_lshl_b32 s44, s44, 5
	s_and_b32 s46, s44, 0xffffffc0
	v_or_b32_e32 v54, s46, v5
	s_sub_i32 s44, s57, s46
	v_or_b32_e32 v58, 14, v54
	v_or_b32_e32 v60, 16, v54
	v_or_b32_e32 v62, 18, v54
	v_or_b32_e32 v64, 20, v54
	v_or_b32_e32 v66, 22, v54
	v_or_b32_e32 v68, 24, v54
	v_or_b32_e32 v72, 26, v54
	v_or_b32_e32 v74, 28, v54
	v_or_b32_e32 v76, 30, v54
	v_or_b32_e32 v92, 32, v54
	v_or_b32_e32 v94, 34, v54
	v_or_b32_e32 v96, 36, v54
	v_or_b32_e32 v98, 38, v54
	s_ashr_i32 s45, s44, 31
	v_ashrrev_i32_e32 v55, 31, v54
	v_or_b32_e32 v44, 2, v54
	v_or_b32_e32 v46, 4, v54
	v_or_b32_e32 v48, 6, v54
	v_or_b32_e32 v50, 8, v54
	v_or_b32_e32 v52, 10, v54
	v_or_b32_e32 v56, 12, v54
	v_or_b32_e32 v100, 40, v54
	v_or_b32_e32 v102, 42, v54
	v_or_b32_e32 v104, 44, v54
	v_or_b32_e32 v106, 46, v54
	v_or_b32_e32 v108, 48, v54
	v_or_b32_e32 v110, 50, v54
	v_or_b32_e32 v112, 52, v54
	v_or_b32_e32 v114, 54, v54
	v_or_b32_e32 v116, 56, v54
	v_or_b32_e32 v118, 58, v54
	v_or_b32_e32 v120, 60, v54
	v_or_b32_e32 v122, 62, v54
	v_ashrrev_i32_e32 v59, 31, v58
	v_ashrrev_i32_e32 v61, 31, v60
	v_ashrrev_i32_e32 v63, 31, v62
	v_ashrrev_i32_e32 v65, 31, v64
	v_ashrrev_i32_e32 v67, 31, v66
	v_ashrrev_i32_e32 v69, 31, v68
	v_ashrrev_i32_e32 v73, 31, v72
	v_ashrrev_i32_e32 v75, 31, v74
	v_ashrrev_i32_e32 v77, 31, v76
	v_ashrrev_i32_e32 v93, 31, v92
	v_ashrrev_i32_e32 v95, 31, v94
	v_ashrrev_i32_e32 v97, 31, v96
	v_ashrrev_i32_e32 v99, 31, v98
	v_lshl_add_u64 v[124:125], s[44:45], 2, v[40:41]
	v_lshlrev_b64 v[54:55], 8, v[54:55]
	v_ashrrev_i32_e32 v45, 31, v44
	v_ashrrev_i32_e32 v47, 31, v46
	v_ashrrev_i32_e32 v49, 31, v48
	v_ashrrev_i32_e32 v51, 31, v50
	v_ashrrev_i32_e32 v53, 31, v52
	v_ashrrev_i32_e32 v57, 31, v56
	v_ashrrev_i32_e32 v101, 31, v100
	v_ashrrev_i32_e32 v103, 31, v102
	v_ashrrev_i32_e32 v105, 31, v104
	v_ashrrev_i32_e32 v107, 31, v106
	v_ashrrev_i32_e32 v109, 31, v108
	v_ashrrev_i32_e32 v111, 31, v110
	v_ashrrev_i32_e32 v113, 31, v112
	v_ashrrev_i32_e32 v115, 31, v114
	v_ashrrev_i32_e32 v117, 31, v116
	v_ashrrev_i32_e32 v119, 31, v118
	v_ashrrev_i32_e32 v121, 31, v120
	v_ashrrev_i32_e32 v123, 31, v122
	v_lshlrev_b64 v[58:59], 8, v[58:59]
	v_lshlrev_b64 v[60:61], 8, v[60:61]
	v_lshlrev_b64 v[62:63], 8, v[62:63]
	v_lshlrev_b64 v[64:65], 8, v[64:65]
	v_lshlrev_b64 v[66:67], 8, v[66:67]
	v_lshlrev_b64 v[68:69], 8, v[68:69]
	v_lshlrev_b64 v[72:73], 8, v[72:73]
	v_lshlrev_b64 v[74:75], 8, v[74:75]
	v_lshlrev_b64 v[76:77], 8, v[76:77]
	v_lshlrev_b64 v[92:93], 8, v[92:93]
	v_lshlrev_b64 v[94:95], 8, v[94:95]
	v_lshlrev_b64 v[96:97], 8, v[96:97]
	v_lshlrev_b64 v[98:99], 8, v[98:99]
	v_lshl_add_u64 v[54:55], v[124:125], 0, v[54:55]
	v_lshlrev_b64 v[44:45], 8, v[44:45]
	v_lshlrev_b64 v[46:47], 8, v[46:47]
	v_lshlrev_b64 v[48:49], 8, v[48:49]
	v_lshlrev_b64 v[50:51], 8, v[50:51]
	v_lshlrev_b64 v[52:53], 8, v[52:53]
	v_lshlrev_b64 v[56:57], 8, v[56:57]
	v_lshlrev_b64 v[100:101], 8, v[100:101]
	v_lshlrev_b64 v[102:103], 8, v[102:103]
	v_lshlrev_b64 v[104:105], 8, v[104:105]
	v_lshlrev_b64 v[106:107], 8, v[106:107]
	v_lshlrev_b64 v[108:109], 8, v[108:109]
	v_lshlrev_b64 v[110:111], 8, v[110:111]
	v_lshlrev_b64 v[112:113], 8, v[112:113]
	v_lshlrev_b64 v[114:115], 8, v[114:115]
	v_lshlrev_b64 v[116:117], 8, v[116:117]
	v_lshlrev_b64 v[118:119], 8, v[118:119]
	v_lshlrev_b64 v[120:121], 8, v[120:121]
	v_lshlrev_b64 v[122:123], 8, v[122:123]
	v_lshl_add_u64 v[58:59], v[124:125], 0, v[58:59]
	v_lshl_add_u64 v[60:61], v[124:125], 0, v[60:61]
	v_lshl_add_u64 v[62:63], v[124:125], 0, v[62:63]
	v_lshl_add_u64 v[64:65], v[124:125], 0, v[64:65]
	v_lshl_add_u64 v[66:67], v[124:125], 0, v[66:67]
	v_lshl_add_u64 v[68:69], v[124:125], 0, v[68:69]
	v_lshl_add_u64 v[72:73], v[124:125], 0, v[72:73]
	v_lshl_add_u64 v[74:75], v[124:125], 0, v[74:75]
	v_lshl_add_u64 v[76:77], v[124:125], 0, v[76:77]
	v_lshl_add_u64 v[92:93], v[124:125], 0, v[92:93]
	v_lshl_add_u64 v[94:95], v[124:125], 0, v[94:95]
	v_lshl_add_u64 v[96:97], v[124:125], 0, v[96:97]
	v_lshl_add_u64 v[98:99], v[124:125], 0, v[98:99]
	v_lshl_add_u64 v[44:45], v[124:125], 0, v[44:45]
	v_lshl_add_u64 v[46:47], v[124:125], 0, v[46:47]
	v_lshl_add_u64 v[48:49], v[124:125], 0, v[48:49]
	v_lshl_add_u64 v[50:51], v[124:125], 0, v[50:51]
	v_lshl_add_u64 v[52:53], v[124:125], 0, v[52:53]
	v_lshl_add_u64 v[56:57], v[124:125], 0, v[56:57]
	v_lshl_add_u64 v[100:101], v[124:125], 0, v[100:101]
	v_lshl_add_u64 v[102:103], v[124:125], 0, v[102:103]
	v_lshl_add_u64 v[104:105], v[124:125], 0, v[104:105]
	v_lshl_add_u64 v[106:107], v[124:125], 0, v[106:107]
	v_lshl_add_u64 v[108:109], v[124:125], 0, v[108:109]
	v_lshl_add_u64 v[110:111], v[124:125], 0, v[110:111]
	v_lshl_add_u64 v[112:113], v[124:125], 0, v[112:113]
	v_lshl_add_u64 v[114:115], v[124:125], 0, v[114:115]
	v_lshl_add_u64 v[116:117], v[124:125], 0, v[116:117]
	v_lshl_add_u64 v[118:119], v[124:125], 0, v[118:119]
	v_lshl_add_u64 v[120:121], v[124:125], 0, v[120:121]
	v_lshl_add_u64 v[122:123], v[124:125], 0, v[122:123]
	global_load_dword v124, v[54:55], off
	global_load_dword v125, v[44:45], off
	global_load_dword v126, v[46:47], off
	global_load_dword v127, v[48:49], off
	global_load_dword v128, v[50:51], off
	global_load_dword v129, v[52:53], off
	global_load_dword v130, v[56:57], off
	s_nop 0
	global_load_dword v58, v[58:59], off
	s_nop 0
	global_load_dword v59, v[60:61], off
	s_nop 0
	global_load_dword v60, v[62:63], off
	global_load_dword v61, v[64:65], off
	s_nop 0
	global_load_dword v62, v[66:67], off
	global_load_dword v63, v[68:69], off
	global_load_dword v64, v[72:73], off
	global_load_dword v65, v[74:75], off
	s_nop 0
	global_load_dword v66, v[76:77], off
	global_load_dword v67, v[92:93], off
	global_load_dword v68, v[94:95], off
	global_load_dword v69, v[96:97], off
	global_load_dword v72, v[98:99], off
	global_load_dword v73, v[100:101], off
	global_load_dword v74, v[102:103], off
	global_load_dword v75, v[104:105], off
	global_load_dword v76, v[106:107], off
	global_load_dword v77, v[108:109], off
	global_load_dword v92, v[110:111], off
	global_load_dword v93, v[112:113], off
	global_load_dword v94, v[114:115], off
	global_load_dword v95, v[116:117], off
	global_load_dword v96, v[118:119], off
	global_load_dword v97, v[120:121], off
	global_load_dword v98, v[122:123], off
	v_add_u32_e32 v50, s44, v78
	v_add_u32_e32 v46, 8, v50
	s_ashr_i32 s47, s46, 31
	v_ashrrev_i32_e32 v47, 31, v46
	s_waitcnt vmcnt(0)
; #define LAS __attribute__((address_space(3)))
; __device__ __forceinline__ unsigned cvt_pk_bf16(float lo, float hi) { unsigned r; asm volatile("v_cvt_pk_bf16_f32 %0, %1, %2" : "=v"(r) : "v"(lo), "v"(hi)); return r; }
; __device__ __forceinline__ void p0_transpose_item(const float* W, int K, int N, bf16_t* WT, LAS float* scr, int item, int lane) {
;     ...
; #pragma unroll
;     for (int i = 0; i < 32; ++i) scr[(2 * i + (lane >> 5)) * 33 + (lane & 31)] = tv[i];
;     asm volatile("s_waitcnt lgkmcnt(0)" ::: "memory");
;     const int c = lane & 7;
; #pragma unroll
;     for (int j = 0; j < 4; ++j) { const int n = (lane >> 3) + 8 * j; const LAS float* s = scr + (8 * c) * 33 + n;
;         u32x4 o; o.x = cvt_pk_bf16(s[0 * 33], s[1 * 33]); o.y = cvt_pk_bf16(s[2 * 33], s[3 * 33]); o.z = cvt_pk_bf16(s[4 * 33], s[5 * 33]); o.w = cvt_pk_bf16(s[6 * 33], s[7 * 33]);
;         *(u32x4*)(WT + (size_t)(n0 + n) * K + k0 + 8 * c) = o; }
;     asm volatile("s_waitcnt lgkmcnt(0)" ::: "memory");
	ds_write2_b32 v71, v124, v125 offset1:66
	ds_write2_b32 v71, v126, v127 offset0:132 offset1:198
	ds_write2_b32 v81, v128, v129 offset0:8 offset1:74
	ds_write2_b32 v81, v130, v58 offset0:140 offset1:206
	ds_write2_b32 v82, v59, v60 offset0:16 offset1:82
	ds_write2_b32 v82, v61, v62 offset0:148 offset1:214
	ds_write2_b32 v83, v63, v64 offset0:24 offset1:90
	ds_write2_b32 v83, v65, v66 offset0:156 offset1:222
	ds_write2_b32 v84, v67, v68 offset0:32 offset1:98
	ds_write2_b32 v84, v69, v72 offset0:164 offset1:230
	ds_write2_b32 v85, v73, v74 offset0:40 offset1:106
	ds_write2_b32 v85, v75, v76 offset0:172 offset1:238
	ds_write2_b32 v86, v77, v92 offset0:48 offset1:114
	ds_write2_b32 v86, v93, v94 offset0:180 offset1:246
	ds_write2_b32 v87, v95, v96 offset0:56 offset1:122
	ds_write2_b32 v87, v97, v98 offset0:188 offset1:254
	v_lshl_add_u64 v[44:45], s[46:47], 1, v[42:43]
	v_add_u32_e32 v48, 16, v50
	v_lshlrev_b64 v[46:47], 7, v[46:47]
	s_waitcnt lgkmcnt(0)
	v_ashrrev_i32_e32 v51, 31, v50
	v_ashrrev_i32_e32 v49, 31, v48
	v_lshl_add_u64 v[56:57], v[44:45], 0, v[46:47]
	ds_read2_b32 v[46:47], v79 offset1:33
	v_lshlrev_b64 v[52:53], 7, v[50:51]
	v_lshlrev_b64 v[54:55], 7, v[48:49]
	s_waitcnt lgkmcnt(0)
	v_cvt_pk_bf16_f32 v46, v46, v47
	ds_read2_b32 v[48:49], v79 offset0:66 offset1:99
	v_lshl_add_u64 v[52:53], v[44:45], 0, v[52:53]
	s_waitcnt lgkmcnt(0)
	v_cvt_pk_bf16_f32 v47, v48, v49
	ds_read2_b32 v[48:49], v79 offset0:132 offset1:165
	s_waitcnt lgkmcnt(0)
	v_cvt_pk_bf16_f32 v48, v48, v49
	ds_read2_b32 v[58:59], v79 offset0:198 offset1:231
	s_waitcnt lgkmcnt(0)
	v_cvt_pk_bf16_f32 v49, v58, v59
	global_store_dwordx4 v[52:53], v[46:49], off
	ds_read2_b32 v[46:47], v79 offset0:8 offset1:41
	v_lshl_add_u64 v[54:55], v[44:45], 0, v[54:55]
	s_waitcnt lgkmcnt(0)
	v_cvt_pk_bf16_f32 v46, v46, v47
	ds_read2_b32 v[48:49], v79 offset0:74 offset1:107
	s_waitcnt lgkmcnt(0)
	v_cvt_pk_bf16_f32 v47, v48, v49
	ds_read2_b32 v[48:49], v79 offset0:140 offset1:173
	s_waitcnt lgkmcnt(0)
	v_cvt_pk_bf16_f32 v48, v48, v49
	ds_read2_b32 v[52:53], v79 offset0:206 offset1:239
	s_waitcnt lgkmcnt(0)
	v_cvt_pk_bf16_f32 v49, v52, v53
	global_store_dwordx4 v[56:57], v[46:49], off
	ds_read2_b32 v[46:47], v79 offset0:16 offset1:49
	v_add_u32_e32 v50, 24, v50
	s_waitcnt lgkmcnt(0)
	v_cvt_pk_bf16_f32 v46, v46, v47
	ds_read2_b32 v[48:49], v79 offset0:82 offset1:115
	s_waitcnt lgkmcnt(0)
	v_cvt_pk_bf16_f32 v47, v48, v49
	ds_read2_b32 v[48:49], v79 offset0:148 offset1:181
	s_waitcnt lgkmcnt(0)
	v_cvt_pk_bf16_f32 v48, v48, v49
	ds_read2_b32 v[52:53], v79 offset0:214 offset1:247
	s_waitcnt lgkmcnt(0)
	v_cvt_pk_bf16_f32 v49, v52, v53
	global_store_dwordx4 v[54:55], v[46:49], off
	ds_read2_b32 v[46:47], v79 offset0:24 offset1:57
	v_ashrrev_i32_e32 v51, 31, v50
	s_waitcnt lgkmcnt(0)
	v_cvt_pk_bf16_f32 v46, v46, v47
	ds_read2_b32 v[48:49], v79 offset0:90 offset1:123
	v_lshlrev_b64 v[50:51], 7, v[50:51]
	s_waitcnt lgkmcnt(0)
	v_cvt_pk_bf16_f32 v47, v48, v49
	ds_read2_b32 v[48:49], v79 offset0:156 offset1:189
	v_lshl_add_u64 v[44:45], v[44:45], 0, v[50:51]
	s_waitcnt lgkmcnt(0)
	v_cvt_pk_bf16_f32 v48, v48, v49
	ds_read2_b32 v[52:53], v79 offset0:222 offset1:255
	s_waitcnt lgkmcnt(0)
	v_cvt_pk_bf16_f32 v49, v52, v53
	global_store_dwordx4 v[44:45], v[46:49], off
	s_waitcnt lgkmcnt(0)
	s_add_i32 s58, s58, s60
	s_add_i32 s57, s57, s55
	s_cmp_gt_i32 s58, 1
	s_cbranch_scc0 .LBB0_30
	s_add_i32 s8, s8, s21
	s_or_b32 s8, s8, 1
	s_lshl_b64 s[44:45], s[8:9], 15
	s_add_u32 s8, s49, s44
	s_addc_u32 s45, s50, s45
	s_lshl_b32 s44, s56, 1
	s_add_u32 s44, s8, s44
	s_addc_u32 s45, s45, 0
	v_lshl_add_u64 v[40:41], v[36:37], 0, s[42:43]
	v_lshl_add_u64 v[42:43], s[44:45], 0, v[2:3]
	s_lshl_b32 s8, s53, 1
	s_sub_i32 s8, s48, s8
	s_sub_i32 s8, s8, 2000
.LBB0_32:
	s_lshr_b32 s42, s8, 31
	s_add_i32 s42, s8, s42
	s_lshl_b32 s42, s42, 5
	s_and_b32 s44, s42, 0xffffffc0
	v_or_b32_e32 v54, s44, v5
	s_sub_i32 s42, s54, s44
	v_or_b32_e32 v58, 14, v54
	v_or_b32_e32 v60, 16, v54
	v_or_b32_e32 v62, 18, v54
	v_or_b32_e32 v64, 20, v54
	v_or_b32_e32 v66, 22, v54
	v_or_b32_e32 v68, 24, v54
	v_or_b32_e32 v72, 26, v54
	v_or_b32_e32 v74, 28, v54
	v_or_b32_e32 v76, 30, v54
	v_or_b32_e32 v92, 32, v54
	v_or_b32_e32 v94, 34, v54
	v_or_b32_e32 v96, 36, v54
	v_or_b32_e32 v98, 38, v54
	s_ashr_i32 s43, s42, 31
	v_ashrrev_i32_e32 v55, 31, v54
	v_or_b32_e32 v44, 2, v54
	v_or_b32_e32 v46, 4, v54
	v_or_b32_e32 v48, 6, v54
	v_or_b32_e32 v50, 8, v54
	v_or_b32_e32 v52, 10, v54
	v_or_b32_e32 v56, 12, v54
	v_or_b32_e32 v100, 40, v54
	v_or_b32_e32 v102, 42, v54
	v_or_b32_e32 v104, 44, v54
	v_or_b32_e32 v106, 46, v54
	v_or_b32_e32 v108, 48, v54
	v_or_b32_e32 v110, 50, v54
	v_or_b32_e32 v112, 52, v54
	v_or_b32_e32 v114, 54, v54
	v_or_b32_e32 v116, 56, v54
	v_or_b32_e32 v118, 58, v54
	v_or_b32_e32 v120, 60, v54
	v_or_b32_e32 v122, 62, v54
	v_ashrrev_i32_e32 v59, 31, v58
	v_ashrrev_i32_e32 v61, 31, v60
	v_ashrrev_i32_e32 v63, 31, v62
	v_ashrrev_i32_e32 v65, 31, v64
	v_ashrrev_i32_e32 v67, 31, v66
	v_ashrrev_i32_e32 v69, 31, v68
	v_ashrrev_i32_e32 v73, 31, v72
	v_ashrrev_i32_e32 v75, 31, v74
	v_ashrrev_i32_e32 v77, 31, v76
	v_ashrrev_i32_e32 v93, 31, v92
	v_ashrrev_i32_e32 v95, 31, v94
	v_ashrrev_i32_e32 v97, 31, v96
	v_ashrrev_i32_e32 v99, 31, v98
	v_lshl_add_u64 v[124:125], s[42:43], 2, v[40:41]
	v_lshlrev_b64 v[54:55], 8, v[54:55]
	v_ashrrev_i32_e32 v45, 31, v44
	v_ashrrev_i32_e32 v47, 31, v46
	v_ashrrev_i32_e32 v49, 31, v48
	v_ashrrev_i32_e32 v51, 31, v50
	v_ashrrev_i32_e32 v53, 31, v52
	v_ashrrev_i32_e32 v57, 31, v56
	v_ashrrev_i32_e32 v101, 31, v100
	v_ashrrev_i32_e32 v103, 31, v102
	v_ashrrev_i32_e32 v105, 31, v104
	v_ashrrev_i32_e32 v107, 31, v106
; __device__ __forceinline__ void p0_transpose_item(const float* W, int K, int N, bf16_t* WT, LAS float* scr, int item, int lane) {
;     const int nblk = N / 32, kb = item / nblk, nb = item % nblk, k0 = 64 * kb, n0 = 32 * nb;
;     float tv[32];
; #pragma unroll
;     for (int i = 0; i < 32; ++i) tv[i] = W[(size_t)(k0 + 2 * i + (lane >> 5)) * N + n0 + (lane & 31)];
	v_ashrrev_i32_e32 v109, 31, v108
	v_ashrrev_i32_e32 v111, 31, v110
	v_ashrrev_i32_e32 v113, 31, v112
	v_ashrrev_i32_e32 v115, 31, v114
	v_ashrrev_i32_e32 v117, 31, v116
	v_ashrrev_i32_e32 v119, 31, v118
	v_ashrrev_i32_e32 v121, 31, v120
	v_ashrrev_i32_e32 v123, 31, v122
	v_lshlrev_b64 v[58:59], 8, v[58:59]
	v_lshlrev_b64 v[60:61], 8, v[60:61]
	v_lshlrev_b64 v[62:63], 8, v[62:63]
	v_lshlrev_b64 v[64:65], 8, v[64:65]
	v_lshlrev_b64 v[66:67], 8, v[66:67]
	v_lshlrev_b64 v[68:69], 8, v[68:69]
	v_lshlrev_b64 v[72:73], 8, v[72:73]
	v_lshlrev_b64 v[74:75], 8, v[74:75]
	v_lshlrev_b64 v[76:77], 8, v[76:77]
	v_lshlrev_b64 v[92:93], 8, v[92:93]
	v_lshlrev_b64 v[94:95], 8, v[94:95]
	v_lshlrev_b64 v[96:97], 8, v[96:97]
	v_lshlrev_b64 v[98:99], 8, v[98:99]
	v_lshl_add_u64 v[54:55], v[124:125], 0, v[54:55]
	v_lshlrev_b64 v[44:45], 8, v[44:45]
	v_lshlrev_b64 v[46:47], 8, v[46:47]
	v_lshlrev_b64 v[48:49], 8, v[48:49]
	v_lshlrev_b64 v[50:51], 8, v[50:51]
	v_lshlrev_b64 v[52:53], 8, v[52:53]
	v_lshlrev_b64 v[56:57], 8, v[56:57]
	v_lshlrev_b64 v[100:101], 8, v[100:101]
	v_lshlrev_b64 v[102:103], 8, v[102:103]
	v_lshlrev_b64 v[104:105], 8, v[104:105]
	v_lshlrev_b64 v[106:107], 8, v[106:107]
	v_lshlrev_b64 v[108:109], 8, v[108:109]
	v_lshlrev_b64 v[110:111], 8, v[110:111]
	v_lshlrev_b64 v[112:113], 8, v[112:113]
	v_lshlrev_b64 v[114:115], 8, v[114:115]
	v_lshlrev_b64 v[116:117], 8, v[116:117]
	v_lshlrev_b64 v[118:119], 8, v[118:119]
	v_lshlrev_b64 v[120:121], 8, v[120:121]
	v_lshlrev_b64 v[122:123], 8, v[122:123]
	v_lshl_add_u64 v[58:59], v[124:125], 0, v[58:59]
	v_lshl_add_u64 v[60:61], v[124:125], 0, v[60:61]
	v_lshl_add_u64 v[62:63], v[124:125], 0, v[62:63]
	v_lshl_add_u64 v[64:65], v[124:125], 0, v[64:65]
	v_lshl_add_u64 v[66:67], v[124:125], 0, v[66:67]
	v_lshl_add_u64 v[68:69], v[124:125], 0, v[68:69]
	v_lshl_add_u64 v[72:73], v[124:125], 0, v[72:73]
	v_lshl_add_u64 v[74:75], v[124:125], 0, v[74:75]
	v_lshl_add_u64 v[76:77], v[124:125], 0, v[76:77]
	v_lshl_add_u64 v[92:93], v[124:125], 0, v[92:93]
	v_lshl_add_u64 v[94:95], v[124:125], 0, v[94:95]
	v_lshl_add_u64 v[96:97], v[124:125], 0, v[96:97]
	v_lshl_add_u64 v[98:99], v[124:125], 0, v[98:99]
	v_lshl_add_u64 v[44:45], v[124:125], 0, v[44:45]
	v_lshl_add_u64 v[46:47], v[124:125], 0, v[46:47]
	v_lshl_add_u64 v[48:49], v[124:125], 0, v[48:49]
	v_lshl_add_u64 v[50:51], v[124:125], 0, v[50:51]
	v_lshl_add_u64 v[52:53], v[124:125], 0, v[52:53]
	v_lshl_add_u64 v[56:57], v[124:125], 0, v[56:57]
	v_lshl_add_u64 v[100:101], v[124:125], 0, v[100:101]
	v_lshl_add_u64 v[102:103], v[124:125], 0, v[102:103]
	v_lshl_add_u64 v[104:105], v[124:125], 0, v[104:105]
	v_lshl_add_u64 v[106:107], v[124:125], 0, v[106:107]
	v_lshl_add_u64 v[108:109], v[124:125], 0, v[108:109]
	v_lshl_add_u64 v[110:111], v[124:125], 0, v[110:111]
	v_lshl_add_u64 v[112:113], v[124:125], 0, v[112:113]
	v_lshl_add_u64 v[114:115], v[124:125], 0, v[114:115]
	v_lshl_add_u64 v[116:117], v[124:125], 0, v[116:117]
	v_lshl_add_u64 v[118:119], v[124:125], 0, v[118:119]
	v_lshl_add_u64 v[120:121], v[124:125], 0, v[120:121]
	v_lshl_add_u64 v[122:123], v[124:125], 0, v[122:123]
	global_load_dword v2, v[54:55], off
	global_load_dword v124, v[44:45], off
	global_load_dword v125, v[46:47], off
	global_load_dword v126, v[48:49], off
	global_load_dword v127, v[50:51], off
	global_load_dword v128, v[52:53], off
	global_load_dword v129, v[56:57], off
	s_nop 0
	global_load_dword v58, v[58:59], off
	s_nop 0
	global_load_dword v59, v[60:61], off
	s_nop 0
	global_load_dword v60, v[62:63], off
	global_load_dword v61, v[64:65], off
	s_nop 0
	global_load_dword v62, v[66:67], off
	global_load_dword v63, v[68:69], off
	global_load_dword v64, v[72:73], off
	global_load_dword v65, v[74:75], off
	s_nop 0
	global_load_dword v66, v[76:77], off
	global_load_dword v67, v[92:93], off
	global_load_dword v68, v[94:95], off
	global_load_dword v69, v[96:97], off
	global_load_dword v72, v[98:99], off
	global_load_dword v73, v[100:101], off
	global_load_dword v74, v[102:103], off
	global_load_dword v75, v[104:105], off
	global_load_dword v76, v[106:107], off
	global_load_dword v77, v[108:109], off
	global_load_dword v92, v[110:111], off
	global_load_dword v93, v[112:113], off
	global_load_dword v94, v[114:115], off
	global_load_dword v95, v[116:117], off
	global_load_dword v96, v[118:119], off
	global_load_dword v97, v[120:121], off
	global_load_dword v98, v[122:123], off
	v_add_u32_e32 v50, s42, v78
	v_add_u32_e32 v46, 8, v50
	s_ashr_i32 s45, s44, 31
	v_ashrrev_i32_e32 v47, 31, v46
	s_waitcnt vmcnt(0)
; #define LAS __attribute__((address_space(3)))
; __device__ __forceinline__ unsigned cvt_pk_bf16(float lo, float hi) { unsigned r; asm volatile("v_cvt_pk_bf16_f32 %0, %1, %2" : "=v"(r) : "v"(lo), "v"(hi)); return r; }
; __device__ __forceinline__ void p0_transpose_item(const float* W, int K, int N, bf16_t* WT, LAS float* scr, int item, int lane) {
;     ...
; #pragma unroll
;     for (int i = 0; i < 32; ++i) scr[(2 * i + (lane >> 5)) * 33 + (lane & 31)] = tv[i];
;     asm volatile("s_waitcnt lgkmcnt(0)" ::: "memory");
;     const int c = lane & 7;
; #pragma unroll
;     for (int j = 0; j < 4; ++j) { const int n = (lane >> 3) + 8 * j; const LAS float* s = scr + (8 * c) * 33 + n;
;         u32x4 o; o.x = cvt_pk_bf16(s[0 * 33], s[1 * 33]); o.y = cvt_pk_bf16(s[2 * 33], s[3 * 33]); o.z = cvt_pk_bf16(s[4 * 33], s[5 * 33]); o.w = cvt_pk_bf16(s[6 * 33], s[7 * 33]);
;         *(u32x4*)(WT + (size_t)(n0 + n) * K + k0 + 8 * c) = o; }
;     asm volatile("s_waitcnt lgkmcnt(0)" ::: "memory");
	ds_write2_b32 v71, v2, v124 offset1:66
	ds_write2_b32 v71, v125, v126 offset0:132 offset1:198
	ds_write2_b32 v81, v127, v128 offset0:8 offset1:74
	ds_write2_b32 v81, v129, v58 offset0:140 offset1:206
	ds_write2_b32 v82, v59, v60 offset0:16 offset1:82
	ds_write2_b32 v82, v61, v62 offset0:148 offset1:214
	ds_write2_b32 v83, v63, v64 offset0:24 offset1:90
	ds_write2_b32 v83, v65, v66 offset0:156 offset1:222
	ds_write2_b32 v84, v67, v68 offset0:32 offset1:98
	ds_write2_b32 v84, v69, v72 offset0:164 offset1:230
	ds_write2_b32 v85, v73, v74 offset0:40 offset1:106
	ds_write2_b32 v85, v75, v76 offset0:172 offset1:238
	ds_write2_b32 v86, v77, v92 offset0:48 offset1:114
	ds_write2_b32 v86, v93, v94 offset0:180 offset1:246
	ds_write2_b32 v87, v95, v96 offset0:56 offset1:122
	ds_write2_b32 v87, v97, v98 offset0:188 offset1:254
	v_lshl_add_u64 v[44:45], s[44:45], 1, v[42:43]
	v_add_u32_e32 v48, 16, v50
	v_lshlrev_b64 v[46:47], 7, v[46:47]
	s_waitcnt lgkmcnt(0)
	v_ashrrev_i32_e32 v51, 31, v50
	v_ashrrev_i32_e32 v49, 31, v48
	v_lshl_add_u64 v[56:57], v[44:45], 0, v[46:47]
	ds_read2_b32 v[46:47], v79 offset1:33
	v_lshlrev_b64 v[52:53], 7, v[50:51]
	v_lshlrev_b64 v[54:55], 7, v[48:49]
	s_waitcnt lgkmcnt(0)
	v_cvt_pk_bf16_f32 v46, v46, v47
	ds_read2_b32 v[48:49], v79 offset0:66 offset1:99
	v_lshl_add_u64 v[52:53], v[44:45], 0, v[52:53]
	s_waitcnt lgkmcnt(0)
	v_cvt_pk_bf16_f32 v47, v48, v49
	ds_read2_b32 v[48:49], v79 offset0:132 offset1:165
	s_waitcnt lgkmcnt(0)
	v_cvt_pk_bf16_f32 v48, v48, v49
	ds_read2_b32 v[58:59], v79 offset0:198 offset1:231
	s_waitcnt lgkmcnt(0)
	v_cvt_pk_bf16_f32 v49, v58, v59
	global_store_dwordx4 v[52:53], v[46:49], off
	ds_read2_b32 v[46:47], v79 offset0:8 offset1:41
	v_lshl_add_u64 v[54:55], v[44:45], 0, v[54:55]
	s_waitcnt lgkmcnt(0)
	v_cvt_pk_bf16_f32 v46, v46, v47
	ds_read2_b32 v[48:49], v79 offset0:74 offset1:107
	s_waitcnt lgkmcnt(0)
	v_cvt_pk_bf16_f32 v47, v48, v49
	ds_read2_b32 v[48:49], v79 offset0:140 offset1:173
	s_waitcnt lgkmcnt(0)
	v_cvt_pk_bf16_f32 v48, v48, v49
	ds_read2_b32 v[52:53], v79 offset0:206 offset1:239
	s_waitcnt lgkmcnt(0)
	v_cvt_pk_bf16_f32 v49, v52, v53
	global_store_dwordx4 v[56:57], v[46:49], off
	ds_read2_b32 v[46:47], v79 offset0:16 offset1:49
	v_add_u32_e32 v50, 24, v50
	s_waitcnt lgkmcnt(0)
	v_cvt_pk_bf16_f32 v46, v46, v47
	ds_read2_b32 v[48:49], v79 offset0:82 offset1:115
	s_waitcnt lgkmcnt(0)
	v_cvt_pk_bf16_f32 v47, v48, v49
	ds_read2_b32 v[48:49], v79 offset0:148 offset1:181
	s_waitcnt lgkmcnt(0)
	v_cvt_pk_bf16_f32 v48, v48, v49
	ds_read2_b32 v[52:53], v79 offset0:214 offset1:247
	s_waitcnt lgkmcnt(0)
	v_cvt_pk_bf16_f32 v49, v52, v53
	global_store_dwordx4 v[54:55], v[46:49], off
	ds_read2_b32 v[46:47], v79 offset0:24 offset1:57
	v_ashrrev_i32_e32 v51, 31, v50
	s_waitcnt lgkmcnt(0)
	v_cvt_pk_bf16_f32 v46, v46, v47
	ds_read2_b32 v[48:49], v79 offset0:90 offset1:123
	v_lshlrev_b64 v[50:51], 7, v[50:51]
	s_waitcnt lgkmcnt(0)
	v_cvt_pk_bf16_f32 v47, v48, v49
	ds_read2_b32 v[48:49], v79 offset0:156 offset1:189
	v_lshl_add_u64 v[44:45], v[44:45], 0, v[50:51]
	s_waitcnt lgkmcnt(0)
	v_cvt_pk_bf16_f32 v48, v48, v49
	ds_read2_b32 v[52:53], v79 offset0:222 offset1:255
	s_waitcnt lgkmcnt(0)
	v_cvt_pk_bf16_f32 v49, v52, v53
	global_store_dwordx4 v[44:45], v[46:49], off
	s_waitcnt lgkmcnt(0)
	s_add_i32 s8, s8, s60
	s_add_i32 s54, s54, s55
	s_cmp_gt_i32 s8, 1
	s_cbranch_scc0 .LBB0_32
	s_branch .LBB0_27

; __device__ __forceinline__ void p0_transpose_item(const float* W, int K, int N, bf16_t* WT, LAS float* scr, int item, int lane) {
;     const int nblk = N / 32, kb = item / nblk, nb = item % nblk, k0 = 64 * kb, n0 = 32 * nb;
;     float tv[32];
; #pragma unroll
;     for (int i = 0; i < 32; ++i) tv[i] = W[(size_t)(k0 + 2 * i + (lane >> 5)) * N + n0 + (lane & 31)];
.LBB0_37:
	s_lshr_b32 s42, s47, 31
	s_add_i32 s42, s47, s42
	s_lshl_b32 s42, s42, 5
	s_and_b32 s44, s42, 0xffffffc0
	v_or_b32_e32 v54, s44, v5
	s_sub_i32 s42, s8, s44
	v_or_b32_e32 v58, 14, v54
	v_or_b32_e32 v60, 16, v54
	v_or_b32_e32 v62, 18, v54
	v_or_b32_e32 v64, 20, v54
	v_or_b32_e32 v66, 22, v54
	v_or_b32_e32 v68, 24, v54
	v_or_b32_e32 v72, 26, v54
	v_or_b32_e32 v74, 28, v54
	v_or_b32_e32 v76, 30, v54
	v_or_b32_e32 v92, 32, v54
	v_or_b32_e32 v94, 34, v54
	v_or_b32_e32 v96, 36, v54
	v_or_b32_e32 v98, 38, v54
	s_ashr_i32 s43, s42, 31
	v_ashrrev_i32_e32 v55, 31, v54
	v_or_b32_e32 v44, 2, v54
	v_or_b32_e32 v46, 4, v54
	v_or_b32_e32 v48, 6, v54
	v_or_b32_e32 v50, 8, v54
	v_or_b32_e32 v52, 10, v54
	v_or_b32_e32 v56, 12, v54
	v_or_b32_e32 v100, 40, v54
	v_or_b32_e32 v102, 42, v54
	v_or_b32_e32 v104, 44, v54
	v_or_b32_e32 v106, 46, v54
	v_or_b32_e32 v108, 48, v54
	v_or_b32_e32 v110, 50, v54
	v_or_b32_e32 v112, 52, v54
	v_or_b32_e32 v114, 54, v54
	v_or_b32_e32 v116, 56, v54
	v_or_b32_e32 v118, 58, v54
	v_or_b32_e32 v120, 60, v54
	v_or_b32_e32 v122, 62, v54
	v_ashrrev_i32_e32 v59, 31, v58
	v_ashrrev_i32_e32 v61, 31, v60
	v_ashrrev_i32_e32 v63, 31, v62
	v_ashrrev_i32_e32 v65, 31, v64
	v_ashrrev_i32_e32 v67, 31, v66
	v_ashrrev_i32_e32 v69, 31, v68
	v_ashrrev_i32_e32 v73, 31, v72
	v_ashrrev_i32_e32 v75, 31, v74
	v_ashrrev_i32_e32 v77, 31, v76
	v_ashrrev_i32_e32 v93, 31, v92
	v_ashrrev_i32_e32 v95, 31, v94
	v_ashrrev_i32_e32 v97, 31, v96
	v_ashrrev_i32_e32 v99, 31, v98
	v_lshl_add_u64 v[124:125], s[42:43], 2, v[40:41]
	v_lshlrev_b64 v[54:55], 8, v[54:55]
	v_ashrrev_i32_e32 v45, 31, v44
	v_ashrrev_i32_e32 v47, 31, v46
	v_ashrrev_i32_e32 v49, 31, v48
	v_ashrrev_i32_e32 v51, 31, v50
	v_ashrrev_i32_e32 v53, 31, v52
	v_ashrrev_i32_e32 v57, 31, v56
	v_ashrrev_i32_e32 v101, 31, v100
	v_ashrrev_i32_e32 v103, 31, v102
	v_ashrrev_i32_e32 v105, 31, v104
	v_ashrrev_i32_e32 v107, 31, v106
	v_ashrrev_i32_e32 v109, 31, v108
	v_ashrrev_i32_e32 v111, 31, v110
	v_ashrrev_i32_e32 v113, 31, v112
	v_ashrrev_i32_e32 v115, 31, v114
	v_ashrrev_i32_e32 v117, 31, v116
	v_ashrrev_i32_e32 v119, 31, v118
	v_ashrrev_i32_e32 v121, 31, v120
	v_ashrrev_i32_e32 v123, 31, v122
	v_lshlrev_b64 v[58:59], 8, v[58:59]
	v_lshlrev_b64 v[60:61], 8, v[60:61]
	v_lshlrev_b64 v[62:63], 8, v[62:63]
	v_lshlrev_b64 v[64:65], 8, v[64:65]
	v_lshlrev_b64 v[66:67], 8, v[66:67]
	v_lshlrev_b64 v[68:69], 8, v[68:69]
	v_lshlrev_b64 v[72:73], 8, v[72:73]
	v_lshlrev_b64 v[74:75], 8, v[74:75]
	v_lshlrev_b64 v[76:77], 8, v[76:77]
	v_lshlrev_b64 v[92:93], 8, v[92:93]
	v_lshlrev_b64 v[94:95], 8, v[94:95]
	v_lshlrev_b64 v[96:97], 8, v[96:97]
	v_lshlrev_b64 v[98:99], 8, v[98:99]
	v_lshl_add_u64 v[54:55], v[124:125], 0, v[54:55]
	v_lshlrev_b64 v[44:45], 8, v[44:45]
	v_lshlrev_b64 v[46:47], 8, v[46:47]
	v_lshlrev_b64 v[48:49], 8, v[48:49]
	v_lshlrev_b64 v[50:51], 8, v[50:51]
	v_lshlrev_b64 v[52:53], 8, v[52:53]
	v_lshlrev_b64 v[56:57], 8, v[56:57]
	v_lshlrev_b64 v[100:101], 8, v[100:101]
	v_lshlrev_b64 v[102:103], 8, v[102:103]
	v_lshlrev_b64 v[104:105], 8, v[104:105]
	v_lshlrev_b64 v[106:107], 8, v[106:107]
	v_lshlrev_b64 v[108:109], 8, v[108:109]
	v_lshlrev_b64 v[110:111], 8, v[110:111]
	v_lshlrev_b64 v[112:113], 8, v[112:113]
	v_lshlrev_b64 v[114:115], 8, v[114:115]
	v_lshlrev_b64 v[116:117], 8, v[116:117]
	v_lshlrev_b64 v[118:119], 8, v[118:119]
	v_lshlrev_b64 v[120:121], 8, v[120:121]
	v_lshlrev_b64 v[122:123], 8, v[122:123]
	v_lshl_add_u64 v[58:59], v[124:125], 0, v[58:59]
	v_lshl_add_u64 v[60:61], v[124:125], 0, v[60:61]
	v_lshl_add_u64 v[62:63], v[124:125], 0, v[62:63]
	v_lshl_add_u64 v[64:65], v[124:125], 0, v[64:65]
	v_lshl_add_u64 v[66:67], v[124:125], 0, v[66:67]
	v_lshl_add_u64 v[68:69], v[124:125], 0, v[68:69]
	v_lshl_add_u64 v[72:73], v[124:125], 0, v[72:73]
	v_lshl_add_u64 v[74:75], v[124:125], 0, v[74:75]
	v_lshl_add_u64 v[76:77], v[124:125], 0, v[76:77]
	v_lshl_add_u64 v[92:93], v[124:125], 0, v[92:93]
	v_lshl_add_u64 v[94:95], v[124:125], 0, v[94:95]
	v_lshl_add_u64 v[96:97], v[124:125], 0, v[96:97]
	v_lshl_add_u64 v[98:99], v[124:125], 0, v[98:99]
	v_lshl_add_u64 v[44:45], v[124:125], 0, v[44:45]
	v_lshl_add_u64 v[46:47], v[124:125], 0, v[46:47]
	v_lshl_add_u64 v[48:49], v[124:125], 0, v[48:49]
	v_lshl_add_u64 v[50:51], v[124:125], 0, v[50:51]
	v_lshl_add_u64 v[52:53], v[124:125], 0, v[52:53]
	v_lshl_add_u64 v[56:57], v[124:125], 0, v[56:57]
	v_lshl_add_u64 v[100:101], v[124:125], 0, v[100:101]
	v_lshl_add_u64 v[102:103], v[124:125], 0, v[102:103]
	v_lshl_add_u64 v[104:105], v[124:125], 0, v[104:105]
	v_lshl_add_u64 v[106:107], v[124:125], 0, v[106:107]
	v_lshl_add_u64 v[108:109], v[124:125], 0, v[108:109]
	v_lshl_add_u64 v[110:111], v[124:125], 0, v[110:111]
	v_lshl_add_u64 v[112:113], v[124:125], 0, v[112:113]
	v_lshl_add_u64 v[114:115], v[124:125], 0, v[114:115]
	v_lshl_add_u64 v[116:117], v[124:125], 0, v[116:117]
	v_lshl_add_u64 v[118:119], v[124:125], 0, v[118:119]
	v_lshl_add_u64 v[120:121], v[124:125], 0, v[120:121]
	v_lshl_add_u64 v[122:123], v[124:125], 0, v[122:123]
	global_load_dword v2, v[54:55], off
	global_load_dword v124, v[44:45], off
	global_load_dword v125, v[46:47], off
	global_load_dword v126, v[48:49], off
	global_load_dword v127, v[50:51], off
	global_load_dword v128, v[52:53], off
	global_load_dword v129, v[56:57], off
	s_nop 0
	global_load_dword v58, v[58:59], off
	s_nop 0
	global_load_dword v59, v[60:61], off
	s_nop 0
	global_load_dword v60, v[62:63], off
	global_load_dword v61, v[64:65], off
	s_nop 0
	global_load_dword v62, v[66:67], off
	global_load_dword v63, v[68:69], off
	global_load_dword v64, v[72:73], off
	global_load_dword v65, v[74:75], off
	s_nop 0
	global_load_dword v66, v[76:77], off
	global_load_dword v67, v[92:93], off
	global_load_dword v68, v[94:95], off
	global_load_dword v69, v[96:97], off
	global_load_dword v72, v[98:99], off
	global_load_dword v73, v[100:101], off
	global_load_dword v74, v[102:103], off
	global_load_dword v75, v[104:105], off
	global_load_dword v76, v[106:107], off
	global_load_dword v77, v[108:109], off
	global_load_dword v92, v[110:111], off
	global_load_dword v93, v[112:113], off
	global_load_dword v94, v[114:115], off
	global_load_dword v95, v[116:117], off
	global_load_dword v96, v[118:119], off
	global_load_dword v97, v[120:121], off
	global_load_dword v98, v[122:123], off
	v_add_u32_e32 v50, s42, v78
	v_add_u32_e32 v46, 8, v50
	s_ashr_i32 s45, s44, 31
	v_ashrrev_i32_e32 v47, 31, v46
	s_waitcnt vmcnt(0)
; #define LAS __attribute__((address_space(3)))
; __device__ __forceinline__ unsigned cvt_pk_bf16(float lo, float hi) { unsigned r; asm volatile("v_cvt_pk_bf16_f32 %0, %1, %2" : "=v"(r) : "v"(lo), "v"(hi)); return r; }
; __device__ __forceinline__ void p0_transpose_item(const float* W, int K, int N, bf16_t* WT, LAS float* scr, int item, int lane) {
;     ...
; #pragma unroll
;     for (int i = 0; i < 32; ++i) scr[(2 * i + (lane >> 5)) * 33 + (lane & 31)] = tv[i];
;     asm volatile("s_waitcnt lgkmcnt(0)" ::: "memory");
;     const int c = lane & 7;
; #pragma unroll
;     for (int j = 0; j < 4; ++j) { const int n = (lane >> 3) + 8 * j; const LAS float* s = scr + (8 * c) * 33 + n;
;         u32x4 o; o.x = cvt_pk_bf16(s[0 * 33], s[1 * 33]); o.y = cvt_pk_bf16(s[2 * 33], s[3 * 33]); o.z = cvt_pk_bf16(s[4 * 33], s[5 * 33]); o.w = cvt_pk_bf16(s[6 * 33], s[7 * 33]);
;         *(u32x4*)(WT + (size_t)(n0 + n) * K + k0 + 8 * c) = o; }
;     asm volatile("s_waitcnt lgkmcnt(0)" ::: "memory");
	ds_write2_b32 v71, v2, v124 offset1:66
	ds_write2_b32 v71, v125, v126 offset0:132 offset1:198
	ds_write2_b32 v81, v127, v128 offset0:8 offset1:74
	ds_write2_b32 v81, v129, v58 offset0:140 offset1:206
	ds_write2_b32 v82, v59, v60 offset0:16 offset1:82
	ds_write2_b32 v82, v61, v62 offset0:148 offset1:214
	ds_write2_b32 v83, v63, v64 offset0:24 offset1:90
	ds_write2_b32 v83, v65, v66 offset0:156 offset1:222
	ds_write2_b32 v84, v67, v68 offset0:32 offset1:98
	ds_write2_b32 v84, v69, v72 offset0:164 offset1:230
	ds_write2_b32 v85, v73, v74 offset0:40 offset1:106
	ds_write2_b32 v85, v75, v76 offset0:172 offset1:238
	ds_write2_b32 v86, v77, v92 offset0:48 offset1:114
	ds_write2_b32 v86, v93, v94 offset0:180 offset1:246
	ds_write2_b32 v87, v95, v96 offset0:56 offset1:122
	ds_write2_b32 v87, v97, v98 offset0:188 offset1:254
	v_lshl_add_u64 v[44:45], s[44:45], 1, v[42:43]
	v_add_u32_e32 v48, 16, v50
	v_lshlrev_b64 v[46:47], 7, v[46:47]
	s_waitcnt lgkmcnt(0)
	v_ashrrev_i32_e32 v51, 31, v50
	v_ashrrev_i32_e32 v49, 31, v48
	v_lshl_add_u64 v[56:57], v[44:45], 0, v[46:47]
	ds_read2_b32 v[46:47], v79 offset1:33
	v_lshlrev_b64 v[52:53], 7, v[50:51]
	v_lshlrev_b64 v[54:55], 7, v[48:49]
	s_waitcnt lgkmcnt(0)
	v_cvt_pk_bf16_f32 v46, v46, v47
	ds_read2_b32 v[48:49], v79 offset0:66 offset1:99
	v_lshl_add_u64 v[52:53], v[44:45], 0, v[52:53]
	s_waitcnt lgkmcnt(0)
	v_cvt_pk_bf16_f32 v47, v48, v49
	ds_read2_b32 v[48:49], v79 offset0:132 offset1:165
	s_waitcnt lgkmcnt(0)
	v_cvt_pk_bf16_f32 v48, v48, v49
	ds_read2_b32 v[58:59], v79 offset0:198 offset1:231
	s_waitcnt lgkmcnt(0)
	v_cvt_pk_bf16_f32 v49, v58, v59
	global_store_dwordx4 v[52:53], v[46:49], off
	ds_read2_b32 v[46:47], v79 offset0:8 offset1:41
	v_lshl_add_u64 v[54:55], v[44:45], 0, v[54:55]
	s_waitcnt lgkmcnt(0)
	v_cvt_pk_bf16_f32 v46, v46, v47
	ds_read2_b32 v[48:49], v79 offset0:74 offset1:107
	s_waitcnt lgkmcnt(0)
	v_cvt_pk_bf16_f32 v47, v48, v49
	ds_read2_b32 v[48:49], v79 offset0:140 offset1:173
	s_waitcnt lgkmcnt(0)
	v_cvt_pk_bf16_f32 v48, v48, v49
	ds_read2_b32 v[52:53], v79 offset0:206 offset1:239
	s_waitcnt lgkmcnt(0)
	v_cvt_pk_bf16_f32 v49, v52, v53
	global_store_dwordx4 v[56:57], v[46:49], off
	ds_read2_b32 v[46:47], v79 offset0:16 offset1:49
	v_add_u32_e32 v50, 24, v50
	s_waitcnt lgkmcnt(0)
	v_cvt_pk_bf16_f32 v46, v46, v47
	ds_read2_b32 v[48:49], v79 offset0:82 offset1:115
	s_waitcnt lgkmcnt(0)
	v_cvt_pk_bf16_f32 v47, v48, v49
	ds_read2_b32 v[48:49], v79 offset0:148 offset1:181
	s_waitcnt lgkmcnt(0)
	v_cvt_pk_bf16_f32 v48, v48, v49
	ds_read2_b32 v[52:53], v79 offset0:214 offset1:247
	s_waitcnt lgkmcnt(0)
	v_cvt_pk_bf16_f32 v49, v52, v53
	global_store_dwordx4 v[54:55], v[46:49], off
	ds_read2_b32 v[46:47], v79 offset0:24 offset1:57
	v_ashrrev_i32_e32 v51, 31, v50
	s_waitcnt lgkmcnt(0)
	v_cvt_pk_bf16_f32 v46, v46, v47
	ds_read2_b32 v[48:49], v79 offset0:90 offset1:123
	v_lshlrev_b64 v[50:51], 7, v[50:51]
	s_waitcnt lgkmcnt(0)
	v_cvt_pk_bf16_f32 v47, v48, v49
	ds_read2_b32 v[48:49], v79 offset0:156 offset1:189
	v_lshl_add_u64 v[44:45], v[44:45], 0, v[50:51]
	s_waitcnt lgkmcnt(0)
	v_cvt_pk_bf16_f32 v48, v48, v49
	ds_read2_b32 v[52:53], v79 offset0:222 offset1:255
	s_waitcnt lgkmcnt(0)
	v_cvt_pk_bf16_f32 v49, v52, v53
	global_store_dwordx4 v[44:45], v[46:49], off
	s_waitcnt lgkmcnt(0)
	s_add_i32 s47, s47, s60
	s_add_i32 s8, s8, s46
	s_cmp_gt_i32 s47, 1
	s_cbranch_scc0 .LBB0_37
	s_branch .LBB0_34

.LBB0_40:
	v_add_u32_e32 v2, s20, v2
	s_movk_i32 s8, 0x2fff
	v_cmp_lt_i32_e32 vcc, s8, v2
	global_store_dwordx4 v[40:41], v[88:91], off
	s_or_b64 s[40:41], vcc, s[40:41]
	v_lshl_add_u64 v[40:41], v[40:41], 0, s[36:37]
	s_andn2_b64 exec, exec, s[40:41]
	s_cbranch_execnz .LBB0_40
	s_branch .LBB0_6
	s_branch .Lmy_pad_LBB041
	s_nop 0
	s_nop 0
	s_nop 0
	s_nop 0
	s_nop 0
	s_nop 0
	s_nop 0

; __global__ void __launch_bounds__(512, 2) fwd_kernel(KArgs a) {
;     ...
;                 for (int o = tid; o < 17 * 64; o += 512) { const int r = o >> 6, cc = o & 63, c2 = (bt % 48) * 64 + cc; float s = a.in[5][l * 3072 + c2];
; #pragma unroll
;                     for (int w = 0; w < 8; ++w) s += red[(w * 17 + r) * 64 + cc];
;                     MOD[((size_t)l * 17 + r) * 3072 + c2] = s; }
.LBB0_51:
	global_load_dword v7, v[2:3], off
	v_ashrrev_i32_e32 v8, 6, v6
	v_add_u32_e32 v10, 0x200, v6
	s_movk_i32 s4, 0x23f
	v_lshl_add_u32 v16, v8, 8, v71
	v_cmp_lt_i32_e64 s[4:5], s4, v6
	v_mov_b32_e32 v6, v10
	ds_read2st64_b32 v[10:11], v16 offset1:17
	ds_read2st64_b32 v[12:13], v16 offset0:34 offset1:51
	ds_read2st64_b32 v[14:15], v16 offset0:68 offset1:85
	ds_read2st64_b32 v[16:17], v16 offset0:102 offset1:119
	v_ashrrev_i32_e32 v9, 31, v8
	v_lshl_add_u64 v[8:9], s[8:9], 0, v[8:9]
	s_or_b64 s[10:11], s[4:5], s[10:11]
	v_mad_u64_u32 v[18:19], s[4:5], v8, s26, v[4:5]
	v_mov_b32_e32 v8, v19
	v_mad_u64_u32 v[8:9], s[4:5], v9, s26, v[8:9]
	v_mov_b32_e32 v19, v8
	s_waitcnt vmcnt(0) lgkmcnt(0)
	v_add_f32_e32 v7, v7, v10
	v_add_f32_e32 v7, v7, v11
	s_waitcnt lgkmcnt(2)
	v_add_f32_e32 v7, v7, v12
	v_add_f32_e32 v7, v7, v13
	s_waitcnt lgkmcnt(1)
	v_add_f32_e32 v7, v7, v14
	v_add_f32_e32 v7, v7, v15
	s_waitcnt lgkmcnt(0)
	v_add_f32_e32 v7, v7, v16
	v_add_f32_e32 v7, v7, v17
	global_store_dword v[18:19], v7, off
	s_andn2_b64 exec, exec, s[10:11]
	s_cbranch_execnz .LBB0_51
	s_branch .LBB0_46

; __global__ void __launch_bounds__(512, 2) fwd_kernel(KArgs a) {
;     ...
;         for (int i = gt; i < 4096 * 33; i += NGT) {
;             const int p = i & 63, e = (i >> 6) % 33, q = (i >> 6) / 33, g = q & 15, d = (q >> 4) & 1, l = q >> 5;
;             const int ig = (l * 2 + d) * 16 + g; const float dt = __expf(a.in[16][ig]), are = a.in[14][ig * 64 + p], aim = a.in[15][ig * 64 + p];
;             const float mg = expf(are * dt * (float)e); float sn, cs; sincosf(aim * dt * (float)e, &sn, &cs);
;             float* o = POW + ((size_t)(ig * 33 + e) * 64 + p) * 2; o[0] = mg * cs; o[1] = mg * sn;
;         }
.LBB0_54:
	s_or_b64 exec, exec, s[4:5]
	v_mul_f32_e32 v16, v16, v17
	v_mul_f32_e32 v16, v16, v18
	v_mul_f32_e32 v17, 0x3fb8aa3b, v16
	s_mov_b32 s4, 0x3fb8aa3b
	v_fma_f32 v18, v16, s4, -v17
	v_rndne_f32_e32 v20, v17
	v_fmac_f32_e32 v18, 0x32a5705f, v16
	v_sub_f32_e32 v17, v17, v20
	v_add_f32_e32 v17, v17, v18
	v_cvt_i32_f32_e32 v18, v20
	v_exp_f32_e32 v17, v17
	s_mov_b32 s4, 0xc2ce8ed0
	v_cmp_ngt_f32_e32 vcc, s4, v16
	s_mov_b32 s4, 0x42b17218
	v_ldexp_f32 v17, v17, v18
	v_cndmask_b32_e32 v17, 0, v17, vcc
	v_cmp_nlt_f32_e32 vcc, s4, v16
	v_mul_f32_e32 v16, v2, v2
	v_fmamk_f32 v18, v16, 0xb94c1982, v9
	v_fmaak_f32 v18, v16, v18, 0xbe2aaa9d
	v_mul_f32_e32 v18, v16, v18
	v_fmac_f32_e32 v2, v2, v18
	v_fmamk_f32 v18, v16, 0x37d75334, v10
	v_fmaak_f32 v18, v16, v18, 0x3d2aabf7
	v_fmaak_f32 v18, v16, v18, 0xbf000004
	v_fma_f32 v16, v16, v18, 1.0
	v_lshlrev_b32_e32 v18, 30, v19
	v_and_b32_e32 v19, 1, v19
	v_cndmask_b32_e32 v17, v13, v17, vcc
	v_cmp_eq_u32_e32 vcc, 0, v19
	v_xor_b32_e32 v15, v15, v7
	s_brev_b32 s4, 1
	v_cndmask_b32_e32 v19, v16, v2, vcc
	v_xor_b32_e32 v2, 0x80000000, v2
	v_cndmask_b32_e32 v2, v2, v16, vcc
	v_and_b32_e32 v20, 0x80000000, v18
	v_xor_b32_e32 v15, v15, v19
	v_bitop3_b32 v2, v2, v18, s4 bitop3:0x78
	s_movk_i32 s4, 0x1f8
	v_xor_b32_e32 v15, v15, v20
	v_cmp_class_f32_e64 vcc, v7, s4
	v_ashrrev_i32_e32 v7, 31, v6
	v_add_u32_e32 v8, s20, v8
	v_cndmask_b32_e32 v2, v14, v2, vcc
	v_cndmask_b32_e32 v15, v14, v15, vcc
	v_lshlrev_b64 v[6:7], 9, v[6:7]
	v_cmp_lt_i32_e32 vcc, s21, v8
	v_readlane_b32 s36, v251, 24
	v_lshl_add_u64 v[6:7], v[4:5], 0, v[6:7]
	v_mul_f32_e32 v16, v17, v2
	v_mul_f32_e32 v17, v17, v15
	s_or_b64 s[14:15], vcc, s[14:15]
	v_readlane_b32 s37, v251, 25
	v_readlane_b32 s38, v251, 26
	v_readlane_b32 s39, v251, 27
	v_readlane_b32 s40, v251, 28
	v_readlane_b32 s41, v251, 29
	v_readlane_b32 s42, v251, 30
	v_readlane_b32 s43, v251, 31
	v_readlane_b32 s44, v251, 32
	v_readlane_b32 s45, v251, 33
	v_readlane_b32 s46, v251, 34
	v_readlane_b32 s47, v251, 35
	v_readlane_b32 s48, v251, 36
	v_readlane_b32 s49, v251, 37
	v_readlane_b32 s50, v251, 38
	v_readlane_b32 s51, v251, 39
	global_store_dwordx2 v[6:7], v[16:17], off
	s_andn2_b64 exec, exec, s[14:15]
	s_cbranch_execz .LBB0_59

; __device__ __forceinline__ void s5_disc(const KArgs& a, int l, int d, int g, int p, float& dt, float& are, float& aim, float& fre, float& fim) {
;     const int ig = (l * 2 + d) * 16 + g;
;     dt = __expf(a.in[16][ig]); are = a.in[14][ig * 64 + p]; aim = a.in[15][ig * 64 + p];
;     const float mag = expf(are * dt); float sn, cs; sincosf(aim * dt, &sn, &cs);
;     const float abr = mag * cs, abi = mag * sn, den = are * are + aim * aim;
;     fre = ((abr - 1.f) * are + abi * aim) / den; fim = (abi * are - (abr - 1.f) * aim) / den;
; }
; __global__ void __launch_bounds__(512, 2) fwd_kernel(KArgs a) {
;     ...
;         for (int i = bid * 16 + (tid & 15); i < 4096 && tid < 16; i += G * 16) {
;             const int p = i & 63, g = (i >> 6) & 15, d = (i >> 10) & 1, l = i >> 11;
;             float dt, are, aim, fre, fim; s5_disc(a, l, d, g, p, dt, are, aim, fre, fim);
;             const size_t ib = ((size_t)((l * 2 + d) * 16 + g) * 64 + p) * 16;
;             for (int j = 0; j < 16; ++j) { const float br = a.in[17][ib + j], bi = a.in[18][ib + j];
;                 BBAR[(ib + j) * 2] = fre * br - fim * bi; BBAR[(ib + j) * 2 + 1] = fre * bi + fim * br; }
;         }
.LBB0_61:
	s_or_b64 exec, exec, s[4:5]
	v_lshlrev_b64 v[22:23], 10, v[6:7]
	v_lshl_or_b32 v22, v8, 4, v22
	v_readlane_b32 s36, v251, 24
	v_lshlrev_b64 v[8:9], 2, v[22:23]
	v_readlane_b32 s38, v251, 26
	v_readlane_b32 s39, v251, 27
	v_readlane_b32 s40, v251, 28
	v_readlane_b32 s41, v251, 29
	v_lshl_add_u64 v[6:7], s[38:39], 0, v[8:9]
	v_mul_f32_e32 v25, v10, v13
	v_lshl_add_u64 v[8:9], s[40:41], 0, v[8:9]
	global_load_dword v24, v[8:9], off
	global_load_dword v26, v[6:7], off
	v_mul_f32_e32 v27, v4, v4
	v_xor_b32_e32 v32, v12, v20
	v_pk_mul_f32 v[12:13], v[10:11], v[10:11]
	v_mov_b32_e32 v28, v11
	v_mul_f32_e32 v11, 0x3fb8aa3b, v25
	v_fmamk_f32 v33, v27, 0xb94c1982, v14
	v_fmamk_f32 v34, v27, 0x37d75334, v15
	s_mov_b32 s4, 0x3fb8aa3b
	v_fma_f32 v36, v25, s4, -v11
	v_rndne_f32_e32 v37, v11
	v_fmaak_f32 v33, v27, v33, 0xbe2aaa9d
	v_fmaak_f32 v34, v27, v34, 0x3d2aabf7
	v_lshlrev_b32_e32 v29, 30, v21
	v_and_b32_e32 v21, 1, v21
	v_fmac_f32_e32 v36, 0x32a5705f, v25
	v_sub_f32_e32 v11, v11, v37
	v_mul_f32_e32 v33, v27, v33
	v_fmaak_f32 v34, v27, v34, 0xbf000004
	v_add_f32_e32 v11, v11, v36
	v_fmac_f32_e32 v4, v4, v33
	v_fma_f32 v27, v27, v34, 1.0
	v_cmp_eq_u32_e32 vcc, 0, v21
	v_cvt_i32_f32_e32 v37, v37
	v_exp_f32_e32 v11, v11
	v_cndmask_b32_e32 v21, v27, v4, vcc
	v_xor_b32_e32 v4, 0x80000000, v4
	v_cndmask_b32_e32 v4, v4, v27, vcc
	s_brev_b32 s4, 1
	v_and_b32_e32 v35, 0x80000000, v29
	v_xor_b32_e32 v21, v32, v21
	v_bitop3_b32 v4, v4, v29, s4 bitop3:0x78
	s_movk_i32 s4, 0x1f8
	v_xor_b32_e32 v21, v21, v35
	v_cmp_class_f32_e64 vcc, v20, s4
	s_mov_b32 s4, 0xc2ce8ed0
	v_ldexp_f32 v11, v11, v37
	v_cndmask_b32_e32 v4, v19, v4, vcc
	v_cndmask_b32_e32 v20, v19, v21, vcc
	v_cmp_ngt_f32_e32 vcc, s4, v25
	s_mov_b32 s4, 0x42b17218
	v_pk_add_f32 v[30:31], v[12:13], v[12:13] op_sel:[0,1] op_sel_hi:[0,1]
	v_cndmask_b32_e32 v11, 0, v11, vcc
	v_cmp_nlt_f32_e32 vcc, s4, v25
	v_lshlrev_b64 v[12:13], 3, v[22:23]
	v_lshl_add_u64 v[22:23], s[14:15], 0, v[12:13]
	v_cndmask_b32_e32 v11, v18, v11, vcc
	v_mul_f32_e32 v21, v11, v20
	v_fma_f32 v20, v11, v4, -1.0
	v_pk_mul_f32 v[28:29], v[28:29], v[20:21] op_sel:[0,1] op_sel_hi:[0,0]
	v_pk_fma_f32 v[32:33], v[10:11], v[20:21], v[28:29]
	v_pk_fma_f32 v[10:11], v[10:11], v[20:21], v[28:29] op_sel_hi:[0,1,1] neg_lo:[0,0,1] neg_hi:[0,0,1]
	v_div_scale_f32 v4, s[4:5], v31, v31, v11
	v_div_scale_f32 v20, s[4:5], v30, v30, v32
	v_rcp_f32_e32 v21, v4
	v_rcp_f32_e32 v25, v20
	v_div_scale_f32 v10, vcc, v11, v31, v11
	v_fma_f32 v28, -v4, v21, 1.0
	v_fma_f32 v29, -v20, v25, 1.0
	v_fmac_f32_e32 v21, v28, v21
	v_div_scale_f32 v27, s[4:5], v32, v30, v32
	v_fmac_f32_e32 v25, v29, v25
	v_mul_f32_e32 v28, v10, v21
	v_mul_f32_e32 v29, v27, v25
	v_fma_f32 v33, -v4, v28, v10
	v_fma_f32 v34, -v20, v29, v27
	v_fmac_f32_e32 v28, v33, v21
	v_fmac_f32_e32 v29, v34, v25
	v_fma_f32 v4, -v4, v28, v10
	v_fma_f32 v10, -v20, v29, v27
	v_div_fmas_f32 v4, v4, v21, v28
	s_mov_b64 vcc, s[4:5]
	v_div_fixup_f32 v11, v4, v31, v11
	v_div_fmas_f32 v4, v10, v25, v29
	v_div_fixup_f32 v10, v4, v30, v32
	s_waitcnt vmcnt(0)
	v_pk_mul_f32 v[20:21], v[10:11], v[24:25] op_sel:[1,0] op_sel_hi:[0,0]
	v_pk_fma_f32 v[24:25], v[10:11], v[26:27], v[20:21] neg_lo:[0,0,1] neg_hi:[0,0,1]
	v_pk_fma_f32 v[20:21], v[10:11], v[26:27], v[20:21] op_sel_hi:[1,0,1]
	v_add_u32_e32 v3, s21, v3
	v_mov_b32_e32 v25, v21
	global_store_dwordx2 v[22:23], v[24:25], off
	global_load_dword v4, v[8:9], off offset:4
	global_load_dword v20, v[6:7], off offset:4
	v_or_b32_e32 v22, 8, v12
	v_mov_b32_e32 v23, v13
	v_lshl_add_u64 v[22:23], s[14:15], 0, v[22:23]
	s_movk_i32 s4, 0xfff
	v_cmp_lt_i32_e32 vcc, s4, v3
	v_readlane_b32 s37, v251, 25
	v_readlane_b32 s42, v251, 30
	v_readlane_b32 s43, v251, 31
	v_readlane_b32 s44, v251, 32
	v_readlane_b32 s45, v251, 33
	v_readlane_b32 s46, v251, 34
	v_readlane_b32 s47, v251, 35
	v_readlane_b32 s48, v251, 36
	v_readlane_b32 s49, v251, 37
	v_readlane_b32 s50, v251, 38
	v_readlane_b32 s51, v251, 39
	s_or_b64 s[16:17], vcc, s[16:17]
	s_waitcnt vmcnt(0)
	v_pk_mul_f32 v[24:25], v[10:11], v[4:5] op_sel:[1,0] op_sel_hi:[0,0]
	v_pk_fma_f32 v[26:27], v[10:11], v[20:21], v[24:25] neg_lo:[0,0,1] neg_hi:[0,0,1]
	v_pk_fma_f32 v[20:21], v[10:11], v[20:21], v[24:25] op_sel_hi:[1,0,1]
	s_nop 0
	v_mov_b32_e32 v27, v21
	global_store_dwordx2 v[22:23], v[26:27], off
	global_load_dword v4, v[8:9], off offset:8
	global_load_dword v20, v[6:7], off offset:8
	v_or_b32_e32 v22, 16, v12
	v_mov_b32_e32 v23, v13
	v_lshl_add_u64 v[22:23], s[14:15], 0, v[22:23]
	s_waitcnt vmcnt(0)
	v_pk_mul_f32 v[24:25], v[10:11], v[4:5] op_sel:[1,0] op_sel_hi:[0,0]
	v_pk_fma_f32 v[26:27], v[10:11], v[20:21], v[24:25] neg_lo:[0,0,1] neg_hi:[0,0,1]
	v_pk_fma_f32 v[20:21], v[10:11], v[20:21], v[24:25] op_sel_hi:[1,0,1]
	s_nop 0
	v_mov_b32_e32 v27, v21
	global_store_dwordx2 v[22:23], v[26:27], off
	global_load_dword v4, v[8:9], off offset:12
	global_load_dword v20, v[6:7], off offset:12
	v_or_b32_e32 v22, 24, v12
	v_mov_b32_e32 v23, v13
	v_lshl_add_u64 v[22:23], s[14:15], 0, v[22:23]
	s_waitcnt vmcnt(0)
	v_pk_mul_f32 v[24:25], v[10:11], v[4:5] op_sel:[1,0] op_sel_hi:[0,0]
	v_pk_fma_f32 v[26:27], v[10:11], v[20:21], v[24:25] neg_lo:[0,0,1] neg_hi:[0,0,1]
	v_pk_fma_f32 v[20:21], v[10:11], v[20:21], v[24:25] op_sel_hi:[1,0,1]
	s_nop 0
	v_mov_b32_e32 v27, v21
	global_store_dwordx2 v[22:23], v[26:27], off
	global_load_dword v4, v[8:9], off offset:16
	global_load_dword v20, v[6:7], off offset:16
	v_or_b32_e32 v22, 32, v12
	v_mov_b32_e32 v23, v13
	v_lshl_add_u64 v[22:23], s[14:15], 0, v[22:23]
	s_waitcnt vmcnt(0)
; __global__ void __launch_bounds__(512, 2) fwd_kernel(KArgs a) {
;     ...
;             for (int j = 0; j < 16; ++j) { const float br = a.in[17][ib + j], bi = a.in[18][ib + j];
;                 BBAR[(ib + j) * 2] = fre * br - fim * bi; BBAR[(ib + j) * 2 + 1] = fre * bi + fim * br; }
	v_pk_mul_f32 v[24:25], v[10:11], v[4:5] op_sel:[1,0] op_sel_hi:[0,0]
	v_pk_fma_f32 v[26:27], v[10:11], v[20:21], v[24:25] neg_lo:[0,0,1] neg_hi:[0,0,1]
	v_pk_fma_f32 v[20:21], v[10:11], v[20:21], v[24:25] op_sel_hi:[1,0,1]
	s_nop 0
	v_mov_b32_e32 v27, v21
	global_store_dwordx2 v[22:23], v[26:27], off
	global_load_dword v4, v[8:9], off offset:20
	global_load_dword v20, v[6:7], off offset:20
	v_or_b32_e32 v22, 40, v12
	v_mov_b32_e32 v23, v13
	v_lshl_add_u64 v[22:23], s[14:15], 0, v[22:23]
	s_waitcnt vmcnt(0)
	v_pk_mul_f32 v[24:25], v[10:11], v[4:5] op_sel:[1,0] op_sel_hi:[0,0]
	v_pk_fma_f32 v[26:27], v[10:11], v[20:21], v[24:25] neg_lo:[0,0,1] neg_hi:[0,0,1]
	v_pk_fma_f32 v[20:21], v[10:11], v[20:21], v[24:25] op_sel_hi:[1,0,1]
	s_nop 0
	v_mov_b32_e32 v27, v21
	global_store_dwordx2 v[22:23], v[26:27], off
	global_load_dword v4, v[8:9], off offset:24
	global_load_dword v20, v[6:7], off offset:24
	v_or_b32_e32 v22, 48, v12
	v_mov_b32_e32 v23, v13
	v_lshl_add_u64 v[22:23], s[14:15], 0, v[22:23]
	s_waitcnt vmcnt(0)
	v_pk_mul_f32 v[24:25], v[10:11], v[4:5] op_sel:[1,0] op_sel_hi:[0,0]
	v_pk_fma_f32 v[26:27], v[10:11], v[20:21], v[24:25] neg_lo:[0,0,1] neg_hi:[0,0,1]
	v_pk_fma_f32 v[20:21], v[10:11], v[20:21], v[24:25] op_sel_hi:[1,0,1]
	s_nop 0
	v_mov_b32_e32 v27, v21
	global_store_dwordx2 v[22:23], v[26:27], off
	global_load_dword v4, v[8:9], off offset:28
	global_load_dword v20, v[6:7], off offset:28
	v_or_b32_e32 v22, 56, v12
	v_mov_b32_e32 v23, v13
	v_lshl_add_u64 v[22:23], s[14:15], 0, v[22:23]
	s_waitcnt vmcnt(0)
	v_pk_mul_f32 v[24:25], v[10:11], v[4:5] op_sel:[1,0] op_sel_hi:[0,0]
	v_pk_fma_f32 v[26:27], v[10:11], v[20:21], v[24:25] neg_lo:[0,0,1] neg_hi:[0,0,1]
	v_pk_fma_f32 v[20:21], v[10:11], v[20:21], v[24:25] op_sel_hi:[1,0,1]
	s_nop 0
	v_mov_b32_e32 v27, v21
	global_store_dwordx2 v[22:23], v[26:27], off
	global_load_dword v4, v[8:9], off offset:32
	global_load_dword v20, v[6:7], off offset:32
	v_or_b32_e32 v22, 64, v12
	v_mov_b32_e32 v23, v13
	v_lshl_add_u64 v[22:23], s[14:15], 0, v[22:23]
	s_waitcnt vmcnt(0)
	v_pk_mul_f32 v[24:25], v[10:11], v[4:5] op_sel:[1,0] op_sel_hi:[0,0]
	v_pk_fma_f32 v[26:27], v[10:11], v[20:21], v[24:25] neg_lo:[0,0,1] neg_hi:[0,0,1]
	v_pk_fma_f32 v[20:21], v[10:11], v[20:21], v[24:25] op_sel_hi:[1,0,1]
	s_nop 0
	v_mov_b32_e32 v27, v21
	global_store_dwordx2 v[22:23], v[26:27], off
	global_load_dword v4, v[8:9], off offset:36
	global_load_dword v20, v[6:7], off offset:36
	v_or_b32_e32 v22, 0x48, v12
	v_mov_b32_e32 v23, v13
	v_lshl_add_u64 v[22:23], s[14:15], 0, v[22:23]
	s_waitcnt vmcnt(0)
	v_pk_mul_f32 v[24:25], v[10:11], v[4:5] op_sel:[1,0] op_sel_hi:[0,0]
	v_pk_fma_f32 v[26:27], v[10:11], v[20:21], v[24:25] neg_lo:[0,0,1] neg_hi:[0,0,1]
	v_pk_fma_f32 v[20:21], v[10:11], v[20:21], v[24:25] op_sel_hi:[1,0,1]
	s_nop 0
	v_mov_b32_e32 v27, v21
	global_store_dwordx2 v[22:23], v[26:27], off
	global_load_dword v4, v[8:9], off offset:40
	global_load_dword v20, v[6:7], off offset:40
	v_or_b32_e32 v22, 0x50, v12
	v_mov_b32_e32 v23, v13
	v_lshl_add_u64 v[22:23], s[14:15], 0, v[22:23]
	s_waitcnt vmcnt(0)
	v_pk_mul_f32 v[24:25], v[10:11], v[4:5] op_sel:[1,0] op_sel_hi:[0,0]
	v_pk_fma_f32 v[26:27], v[10:11], v[20:21], v[24:25] neg_lo:[0,0,1] neg_hi:[0,0,1]
	v_pk_fma_f32 v[20:21], v[10:11], v[20:21], v[24:25] op_sel_hi:[1,0,1]
	s_nop 0
	v_mov_b32_e32 v27, v21
	global_store_dwordx2 v[22:23], v[26:27], off
	global_load_dword v4, v[8:9], off offset:44
	global_load_dword v20, v[6:7], off offset:44
	v_or_b32_e32 v22, 0x58, v12
	v_mov_b32_e32 v23, v13
	v_lshl_add_u64 v[22:23], s[14:15], 0, v[22:23]
	s_waitcnt vmcnt(0)
	v_pk_mul_f32 v[24:25], v[10:11], v[4:5] op_sel:[1,0] op_sel_hi:[0,0]
	v_pk_fma_f32 v[26:27], v[10:11], v[20:21], v[24:25] neg_lo:[0,0,1] neg_hi:[0,0,1]
	v_pk_fma_f32 v[20:21], v[10:11], v[20:21], v[24:25] op_sel_hi:[1,0,1]
	s_nop 0
	v_mov_b32_e32 v27, v21
	global_store_dwordx2 v[22:23], v[26:27], off
	global_load_dword v4, v[8:9], off offset:48
	global_load_dword v20, v[6:7], off offset:48
	v_or_b32_e32 v22, 0x60, v12
	v_mov_b32_e32 v23, v13
	v_lshl_add_u64 v[22:23], s[14:15], 0, v[22:23]
	s_waitcnt vmcnt(0)
	v_pk_mul_f32 v[24:25], v[10:11], v[4:5] op_sel:[1,0] op_sel_hi:[0,0]
	v_pk_fma_f32 v[26:27], v[10:11], v[20:21], v[24:25] neg_lo:[0,0,1] neg_hi:[0,0,1]
	v_pk_fma_f32 v[20:21], v[10:11], v[20:21], v[24:25] op_sel_hi:[1,0,1]
	s_nop 0
	v_mov_b32_e32 v27, v21
	global_store_dwordx2 v[22:23], v[26:27], off
	global_load_dword v4, v[8:9], off offset:52
	global_load_dword v20, v[6:7], off offset:52
	v_or_b32_e32 v22, 0x68, v12
	v_mov_b32_e32 v23, v13
	v_lshl_add_u64 v[22:23], s[14:15], 0, v[22:23]
	s_waitcnt vmcnt(0)
	v_pk_mul_f32 v[24:25], v[10:11], v[4:5] op_sel:[1,0] op_sel_hi:[0,0]
	v_pk_fma_f32 v[26:27], v[10:11], v[20:21], v[24:25] neg_lo:[0,0,1] neg_hi:[0,0,1]
	v_pk_fma_f32 v[20:21], v[10:11], v[20:21], v[24:25] op_sel_hi:[1,0,1]
	s_nop 0
	v_mov_b32_e32 v27, v21
	global_store_dwordx2 v[22:23], v[26:27], off
	global_load_dword v4, v[8:9], off offset:56
	global_load_dword v20, v[6:7], off offset:56
	v_or_b32_e32 v22, 0x70, v12
	v_mov_b32_e32 v23, v13
	v_lshl_add_u64 v[22:23], s[14:15], 0, v[22:23]
	v_or_b32_e32 v12, 0x78, v12
	s_waitcnt vmcnt(0)
	v_pk_mul_f32 v[24:25], v[10:11], v[4:5] op_sel:[1,0] op_sel_hi:[0,0]
	v_pk_fma_f32 v[26:27], v[10:11], v[20:21], v[24:25] neg_lo:[0,0,1] neg_hi:[0,0,1]
	v_pk_fma_f32 v[20:21], v[10:11], v[20:21], v[24:25] op_sel_hi:[1,0,1]
	s_nop 0
	v_mov_b32_e32 v27, v21
	global_store_dwordx2 v[22:23], v[26:27], off
	global_load_dword v4, v[8:9], off offset:60
	s_nop 0
	global_load_dword v6, v[6:7], off offset:60
	v_lshl_add_u64 v[8:9], s[14:15], 0, v[12:13]
	s_waitcnt vmcnt(0)
	v_pk_mul_f32 v[12:13], v[10:11], v[4:5] op_sel:[1,0] op_sel_hi:[0,0]
	v_pk_fma_f32 v[20:21], v[10:11], v[6:7], v[12:13] neg_lo:[0,0,1] neg_hi:[0,0,1]
	v_pk_fma_f32 v[6:7], v[10:11], v[6:7], v[12:13] op_sel_hi:[1,0,1]
	s_nop 0
	v_mov_b32_e32 v21, v7
	global_store_dwordx2 v[8:9], v[20:21], off
	s_andn2_b64 exec, exec, s[16:17]
	s_cbranch_execz .LBB0_66

; #define LAS __attribute__((address_space(3)))
; __global__ void __launch_bounds__(512, 2) fwd_kernel(KArgs a) {
;     ...
;             LAS float* red = (LAS float*)lds;
; #pragma unroll
;             for (int q = 0; q < 32; ++q) red[(pc * 64 + lane) * 33 + q] = acc[q];
;             __syncthreads();
;             {
; #pragma unroll
;                 for (int qq = 0; qq < 4; ++qq) { const int q = wave * 4 + qq; float s = 0.f;
; #pragma unroll
;                     for (int w = 0; w < 8; ++w) s += red[(w * 64 + lane) * 33 + q];
;                     KT[((size_t)((l * 16 + g) * 2 + d) * 32 + q) * 256 + i * 16 + j] = s; }
;             }
;             __syncthreads();
.LBB0_68:
	s_lshl_b32 s4, s34, 1
	s_or_b32 s4, s4, s35
	s_or_b32 s4, s4, s33
	s_ashr_i32 s5, s4, 31
	s_lshl_b64 s[4:5], s[4:5], 15
	s_add_u32 s4, s21, s4
	s_addc_u32 s5, s28, s5
	v_lshlrev_b32_e32 v2, 2, v1
	s_lshl_b32 s24, s31, 8
	v_bitop3_b32 v2, s24, v57, v2 bitop3:0xc8
	ds_write2_b32 v53, v8, v9 offset1:1
	ds_write2_b32 v53, v10, v11 offset0:2 offset1:3
	ds_write2_b32 v53, v12, v13 offset0:4 offset1:5
	ds_write2_b32 v53, v14, v15 offset0:6 offset1:7
	ds_write2_b32 v53, v16, v17 offset0:8 offset1:9
	ds_write2_b32 v53, v18, v19 offset0:10 offset1:11
	ds_write2_b32 v53, v20, v21 offset0:12 offset1:13
	ds_write2_b32 v53, v22, v23 offset0:14 offset1:15
	ds_write2_b32 v53, v24, v25 offset0:16 offset1:17
	ds_write2_b32 v53, v26, v27 offset0:18 offset1:19
	ds_write2_b32 v53, v28, v29 offset0:20 offset1:21
	ds_write2_b32 v53, v30, v31 offset0:22 offset1:23
	ds_write2_b32 v53, v32, v33 offset0:24 offset1:25
	ds_write2_b32 v53, v34, v35 offset0:26 offset1:27
	ds_write2_b32 v53, v44, v45 offset0:28 offset1:29
	ds_write2_b32 v53, v46, v47 offset0:30 offset1:31
	v_lshl_add_u64 v[8:9], s[4:5], 0, v[2:3]
	v_mov_b32_e32 v7, v3
	s_waitcnt lgkmcnt(0)
	s_barrier
	v_lshl_add_u64 v[8:9], v[8:9], 0, v[6:7]
	ds_read_b32 v2, v54
	ds_read_b32 v7, v54 offset:8448
	ds_read_b32 v10, v54 offset:16896
	ds_read_b32 v11, v54 offset:25344
	ds_read_b32 v12, v54 offset:33792
	ds_read_b32 v13, v54 offset:42240
	ds_read_b32 v14, v54 offset:50688
	ds_read_b32 v15, v54 offset:59136
	s_waitcnt lgkmcnt(7)
	v_add_f32_e32 v2, 0, v2
	s_waitcnt lgkmcnt(6)
	v_add_f32_e32 v2, v2, v7
	s_waitcnt lgkmcnt(5)
	v_add_f32_e32 v2, v2, v10
	s_waitcnt lgkmcnt(4)
	v_add_f32_e32 v2, v2, v11
	s_waitcnt lgkmcnt(3)
	v_add_f32_e32 v2, v2, v12
	s_waitcnt lgkmcnt(2)
	v_add_f32_e32 v2, v2, v13
	s_waitcnt lgkmcnt(1)
	v_add_f32_e32 v2, v2, v14
	s_waitcnt lgkmcnt(0)
	v_add_f32_e32 v2, v2, v15
	v_lshl_add_u64 v[10:11], v[8:9], 0, s[8:9]
	global_store_dword v[10:11], v2, off
	ds_read_b32 v2, v54 offset:4
	ds_read_b32 v7, v54 offset:8452
	ds_read_b32 v10, v54 offset:16900
	ds_read_b32 v11, v54 offset:25348
	ds_read_b32 v12, v54 offset:33796
	ds_read_b32 v13, v54 offset:42244
	ds_read_b32 v14, v54 offset:50692
	ds_read_b32 v15, v54 offset:59140
	s_waitcnt lgkmcnt(0)
	v_add_f32_e32 v2, 0, v2
	v_add_f32_e32 v2, v2, v7
	v_add_f32_e32 v2, v2, v10
	v_add_f32_e32 v2, v2, v11
	v_add_f32_e32 v2, v2, v12
	v_add_f32_e32 v2, v2, v13
	v_add_f32_e32 v2, v2, v14
	v_add_f32_e32 v2, v2, v15
	v_lshl_add_u64 v[10:11], v[8:9], 0, s[10:11]
	global_store_dword v[10:11], v2, off
	ds_read_b32 v2, v54 offset:8
	ds_read_b32 v7, v54 offset:8456
	ds_read_b32 v10, v54 offset:16904
	ds_read_b32 v11, v54 offset:25352
	ds_read_b32 v12, v54 offset:33800
	ds_read_b32 v13, v54 offset:42248
	ds_read_b32 v14, v54 offset:50696
	ds_read_b32 v15, v54 offset:59144
	s_waitcnt lgkmcnt(0)
	v_add_f32_e32 v2, 0, v2
	v_add_f32_e32 v2, v2, v7
	v_add_f32_e32 v2, v2, v10
	v_add_f32_e32 v2, v2, v11
	v_add_f32_e32 v2, v2, v12
	v_add_f32_e32 v2, v2, v13
	v_add_f32_e32 v2, v2, v14
	v_add_f32_e32 v2, v2, v15
	v_lshl_add_u64 v[10:11], v[8:9], 0, s[14:15]
	global_store_dword v[10:11], v2, off
	ds_read_b32 v2, v54 offset:12
	ds_read_b32 v7, v54 offset:8460
	ds_read_b32 v10, v54 offset:16908
	ds_read_b32 v11, v54 offset:25356
	ds_read_b32 v12, v54 offset:33804
	ds_read_b32 v13, v54 offset:42252
	ds_read_b32 v14, v54 offset:50700
	ds_read_b32 v15, v54 offset:59148
	s_waitcnt lgkmcnt(0)
	v_add_f32_e32 v2, 0, v2
	v_add_f32_e32 v2, v2, v7
	v_add_f32_e32 v2, v2, v10
	v_add_f32_e32 v2, v2, v11
	v_add_f32_e32 v2, v2, v12
	v_add_f32_e32 v2, v2, v13
	v_add_f32_e32 v2, v2, v14
	s_add_i32 s31, s31, s74
	v_readlane_b32 s36, v251, 24
	v_add_f32_e32 v2, v2, v15
	v_lshl_add_u64 v[8:9], v[8:9], 0, s[16:17]
	s_cmpk_gt_i32 s31, 0xff
	v_add_u32_e32 v50, s13, v50
	v_readlane_b32 s37, v251, 25
	v_readlane_b32 s38, v251, 26
	v_readlane_b32 s39, v251, 27
	v_readlane_b32 s40, v251, 28
	v_readlane_b32 s41, v251, 29
	v_readlane_b32 s42, v251, 30
	v_readlane_b32 s43, v251, 31
	v_readlane_b32 s44, v251, 32
	v_readlane_b32 s45, v251, 33
	v_readlane_b32 s46, v251, 34
	v_readlane_b32 s47, v251, 35
	v_readlane_b32 s48, v251, 36
	v_readlane_b32 s49, v251, 37
	v_readlane_b32 s50, v251, 38
	v_readlane_b32 s51, v251, 39
	global_store_dword v[8:9], v2, off
	s_waitcnt lgkmcnt(0)
	s_barrier
	s_cbranch_scc1 .LBB0_79

; __device__ __forceinline__ unsigned cvt_pk_bf16(float lo, float hi) { unsigned r; asm volatile("v_cvt_pk_bf16_f32 %0, %1, %2" : "=v"(r) : "v"(lo), "v"(hi)); return r; }
; __global__ void __launch_bounds__(512, 2) fwd_kernel(KArgs a) {
;     ...
;             for (int row = gw; row < MH; row += NGW) {
;                 const bool isc = row >= ML; const int rr = isc ? row - ML : row;
;                 const float* xr = (isc ? xcin : xin) + (size_t)rr * 1024;
;                 const float* md = modl + (size_t)(isc ? 16 : hf * HB + (row >> 11)) * 3072;
;                 const float* ng = a.in[6] + l * 1024;
;                 f32x4 v[4]; float ss = 0.f;
; #pragma unroll
;                 for (int j = 0; j < 4; ++j) { v[j] = *(const f32x4*)(xr + 4 * lane + 256 * j); ss += (v[j][0] * v[j][0] + v[j][1] * v[j][1]) + (v[j][2] * v[j][2] + v[j][3] * v[j][3]); }
;                 const float rinv = rsqrtf(wave_sum(ss) * (1.f / 1024.f) + EPS);
; #pragma unroll
;                 for (int j = 0; j < 4; ++j) { const int c = 4 * lane + 256 * j; const f32x4 gg = *(const f32x4*)(ng + c), sh = *(const f32x4*)(md + c), sc = *(const f32x4*)(md + 1024 + c);
;                     const f32x4 o = v[j] * rinv * gg * (sc + 1.f) + sh; u32x2 w; w.x = cvt_pk_bf16(o[0], o[1]); w.y = cvt_pk_bf16(o[2], o[3]);
;                     *(u32x2*)(HZ + (size_t)row * 1024 + c) = w; }
;             } }
.LBB0_219:
	s_add_i32 s8, s10, 0xffffc000
	s_ashr_i32 s9, s10, 11
	s_cmpk_gt_i32 s10, 0x3fff
	s_cselect_b32 s8, s8, s10
	s_cselect_b32 s13, s57, s53
	s_cselect_b32 s14, s56, s52
	s_cselect_b32 s15, 16, s9
	s_ashr_i32 s9, s8, 31
	s_lshl_b64 s[8:9], s[8:9], 12
	s_add_u32 s8, s14, s8
	s_addc_u32 s9, s13, s9
	global_load_dwordx4 v[20:23], v[2:3], off
	global_load_dwordx4 v[24:27], v0, s[8:9]
	global_load_dwordx4 v[28:31], v0, s[8:9] offset:1024
	global_load_dwordx4 v[32:35], v0, s[8:9] offset:3072
	global_load_dwordx4 v[36:39], v0, s[8:9] offset:2048
	s_mul_hi_i32 s16, s15, 0x3000
	s_mulk_i32 s15, 0x3000
	s_add_u32 s14, s4, s15
	s_addc_u32 s15, s5, s16
	s_add_u32 s8, s14, 0x1000
	s_addc_u32 s9, s15, 0
	v_lshl_add_u64 v[48:49], s[14:15], 0, v[0:1]
	v_lshl_add_u64 v[44:45], s[8:9], 0, v[0:1]
	global_load_dwordx4 v[40:43], v[48:49], off
	v_lshl_add_u64 v[50:51], s[8:9], 0, v[6:7]
	global_load_dwordx4 v[44:47], v[44:45], off
	s_add_i32 s10, s10, s60
	s_cmpk_gt_i32 s10, 0x47ff
	s_waitcnt vmcnt(0)
	v_pk_mul_f32 v[52:53], v[26:27], v[26:27]
	v_pk_mul_f32 v[54:55], v[24:25], v[24:25]
	v_pk_mul_f32 v[56:57], v[30:31], v[30:31]
	v_pk_mul_f32 v[58:59], v[28:29], v[28:29]
	v_pk_mov_b32 v[64:65], v[54:55], v[52:53] op_sel:[1,0]
	v_mov_b32_e32 v55, v53
	v_pk_mov_b32 v[52:53], v[58:59], v[56:57] op_sel:[1,0]
	v_mov_b32_e32 v59, v57
	v_mul_f32_e32 v63, v32, v32
	v_mul_f32_e32 v60, v37, v37
	v_mul_f32_e32 v62, v39, v39
	v_pk_add_f32 v[54:55], v[64:65], v[54:55]
	v_pk_add_f32 v[52:53], v[52:53], v[58:59]
	v_mul_f32_e32 v66, v33, v33
	v_mul_f32_e32 v67, v34, v34
	v_mul_f32_e32 v68, v35, v35
	v_pk_fma_f32 v[56:57], v[36:37], v[36:37], v[60:61] op_sel_hi:[1,1,0]
	v_pk_fma_f32 v[60:61], v[38:39], v[38:39], v[62:63] op_sel_hi:[1,1,0]
	v_pk_add_f32 v[54:55], v[54:55], v[54:55] op_sel:[0,1] op_sel_hi:[1,0]
	v_pk_add_f32 v[52:53], v[52:53], v[52:53] op_sel:[0,1] op_sel_hi:[1,0]
	v_mov_b32_e32 v57, v67
	v_mov_b32_e32 v61, v68
	v_mov_b32_e32 v55, v63
	v_mov_b32_e32 v53, v66
	v_pk_add_f32 v[56:57], v[56:57], v[60:61]
	v_pk_add_f32 v[52:53], v[54:55], v[52:53]
	s_waitcnt lgkmcnt(0)
	v_pk_add_f32 v[44:45], v[44:45], 1.0 op_sel_hi:[1,0]
	v_pk_add_f32 v[52:53], v[52:53], v[56:57]
	v_pk_add_f32 v[46:47], v[46:47], 1.0 op_sel_hi:[1,0]
	v_add_f32_e32 v52, v52, v53
	ds_bpermute_b32 v53, v13, v52
	s_waitcnt lgkmcnt(0)
	v_add_f32_e32 v52, v52, v53
	ds_bpermute_b32 v53, v14, v52
	s_waitcnt lgkmcnt(0)
	v_add_f32_e32 v52, v52, v53
	ds_bpermute_b32 v53, v15, v52
	s_waitcnt lgkmcnt(0)
	v_add_f32_e32 v52, v52, v53
	ds_bpermute_b32 v53, v16, v52
	s_waitcnt lgkmcnt(0)
	v_add_f32_e32 v52, v52, v53
	ds_bpermute_b32 v53, v17, v52
	s_waitcnt lgkmcnt(0)
	v_add_f32_e32 v52, v52, v53
	ds_bpermute_b32 v53, v18, v52
	s_waitcnt lgkmcnt(0)
	v_add_f32_e32 v52, v52, v53
	v_fmamk_f32 v52, v52, 0x3a800000, v19
	v_mul_f32_e32 v53, 0x4b800000, v52
	v_cmp_gt_f32_e32 vcc, s11, v52
	s_nop 1
	v_cndmask_b32_e32 v52, v52, v53, vcc
	v_rsq_f32_e32 v52, v52
	s_nop 0
	v_mul_f32_e32 v53, 0x45800000, v52
	v_cndmask_b32_e32 v52, v52, v53, vcc
	v_pk_mul_f32 v[24:25], v[52:53], v[24:25] op_sel_hi:[0,1]
	v_pk_mul_f32 v[26:27], v[52:53], v[26:27] op_sel_hi:[0,1]
	v_pk_mul_f32 v[20:21], v[20:21], v[24:25]
	v_pk_mul_f32 v[22:23], v[22:23], v[26:27]
	v_pk_fma_f32 v[20:21], v[44:45], v[20:21], v[40:41]
	v_pk_fma_f32 v[22:23], v[46:47], v[22:23], v[42:43]
	v_cvt_pk_bf16_f32 v20, v20, v21
	v_pk_mul_f32 v[28:29], v[52:53], v[28:29] op_sel_hi:[0,1]
	v_cvt_pk_bf16_f32 v21, v22, v23
	global_store_dwordx2 v[4:5], v[20:21], off
	global_load_dwordx4 v[20:23], v[2:3], off offset:1024
	s_nop 0
	global_load_dwordx4 v[24:27], v[50:51], off
	global_load_dwordx4 v[40:43], v[48:49], off offset:1024
	v_pk_mul_f32 v[30:31], v[52:53], v[30:31] op_sel_hi:[0,1]
	v_lshl_add_u64 v[44:45], s[8:9], 0, v[8:9]
	v_pk_mul_f32 v[36:37], v[52:53], v[36:37] op_sel_hi:[0,1]
	v_pk_mul_f32 v[38:39], v[52:53], v[38:39] op_sel_hi:[0,1]
	v_pk_mul_f32 v[32:33], v[52:53], v[32:33] op_sel_hi:[0,1]
	v_pk_mul_f32 v[34:35], v[52:53], v[34:35] op_sel_hi:[0,1]
	s_waitcnt vmcnt(0)
	v_pk_mul_f32 v[20:21], v[20:21], v[28:29]
	s_waitcnt lgkmcnt(0)
	v_pk_add_f32 v[24:25], v[24:25], 1.0 op_sel_hi:[1,0]
	v_pk_mul_f32 v[22:23], v[22:23], v[30:31]
	v_pk_add_f32 v[26:27], v[26:27], 1.0 op_sel_hi:[1,0]
	v_pk_fma_f32 v[20:21], v[24:25], v[20:21], v[40:41]
	v_pk_fma_f32 v[22:23], v[26:27], v[22:23], v[42:43]
	v_cvt_pk_bf16_f32 v20, v20, v21
	v_lshl_add_u64 v[40:41], s[8:9], 0, v[10:11]
	v_cvt_pk_bf16_f32 v21, v22, v23
	global_store_dwordx2 v[4:5], v[20:21], off offset:512
	global_load_dwordx4 v[20:23], v[2:3], off offset:2048
	s_nop 0
	global_load_dwordx4 v[24:27], v[44:45], off
	global_load_dwordx4 v[28:31], v[48:49], off offset:2048
	s_waitcnt vmcnt(0)
	v_pk_mul_f32 v[20:21], v[20:21], v[36:37]
	s_waitcnt lgkmcnt(0)
	v_pk_add_f32 v[24:25], v[24:25], 1.0 op_sel_hi:[1,0]
	v_pk_mul_f32 v[22:23], v[22:23], v[38:39]
	v_pk_add_f32 v[26:27], v[26:27], 1.0 op_sel_hi:[1,0]
	v_pk_fma_f32 v[20:21], v[24:25], v[20:21], v[28:29]
	v_pk_fma_f32 v[22:23], v[26:27], v[22:23], v[30:31]
	v_cvt_pk_bf16_f32 v20, v20, v21
	s_nop 0
	v_cvt_pk_bf16_f32 v21, v22, v23
	global_store_dwordx2 v[4:5], v[20:21], off offset:1024
	global_load_dwordx4 v[20:23], v[2:3], off offset:3072
	s_nop 0
	global_load_dwordx4 v[24:27], v[40:41], off
	global_load_dwordx4 v[28:31], v[48:49], off offset:3072
	s_waitcnt vmcnt(0)
	v_pk_mul_f32 v[20:21], v[20:21], v[32:33]
	s_waitcnt lgkmcnt(0)
	v_pk_add_f32 v[24:25], v[24:25], 1.0 op_sel_hi:[1,0]
	v_pk_mul_f32 v[22:23], v[22:23], v[34:35]
	v_pk_add_f32 v[26:27], v[26:27], 1.0 op_sel_hi:[1,0]
	v_pk_fma_f32 v[20:21], v[24:25], v[20:21], v[28:29]
	v_pk_fma_f32 v[22:23], v[26:27], v[22:23], v[30:31]
	v_cvt_pk_bf16_f32 v20, v20, v21
	s_nop 0
	v_cvt_pk_bf16_f32 v21, v22, v23
	global_store_dwordx2 v[4:5], v[20:21], off offset:1536
	v_lshl_add_u64 v[4:5], v[4:5], 0, s[6:7]
	s_cbranch_scc0 .LBB0_219

; __device__ __forceinline__ unsigned cvt_pk_bf16(float lo, float hi) { unsigned r; asm volatile("v_cvt_pk_bf16_f32 %0, %1, %2" : "=v"(r) : "v"(lo), "v"(hi)); return r; }
;     __device__ __forceinline__ bool operator()(f32x4 (&acc)[2][2][4][2], const Unit& u, int wr, int wc, int fr, int fq) const {
;         const int row0 = u.pm * BM + wr * 64 + fr, col0 = u.pn * BM + wc * 32 + 8 * fq;
; #pragma unroll
;         for (int ai = 0; ai < 2; ++ai)
; #pragma unroll
;             for (int m = 0; m < 4; ++m) { bf16_t* rowp = O + (size_t)(row0 + ai * HALF + m * 16) * ldc + col0;
; #pragma unroll
;                 for (int bj = 0; bj < 2; ++bj) { f32x4 v0 = acc[ai][bj][m][0], v1 = acc[ai][bj][m][1]; u32x4 w;
;                     if (col0 + bj * HALF >= OFF_MERGE) {
;                         int lo = __builtin_amdgcn_cvt_pk_fp8_f32(v0[0], v0[1], 0, false); lo = __builtin_amdgcn_cvt_pk_fp8_f32(v0[2], v0[3], lo, true);
;                         int hi = __builtin_amdgcn_cvt_pk_fp8_f32(v1[0], v1[1], 0, false); hi = __builtin_amdgcn_cvt_pk_fp8_f32(v1[2], v1[3], hi, true);
;                         *(u32x2*)((unsigned char*)(O + (size_t)(row0 + ai * HALF + m * 16) * ldc + OFF_MERGE) + (col0 + bj * HALF - OFF_MERGE)) = (u32x2){(unsigned)lo, (unsigned)hi};
;                         continue; }
;                     w.x = cvt_pk_bf16(v0[0], v0[1]); w.y = cvt_pk_bf16(v0[2], v0[3]); w.z = cvt_pk_bf16(v1[0], v1[1]); w.w = cvt_pk_bf16(v1[2], v1[3]);
;                     *(u32x4*)(rowp + bj * HALF) = w; } }
.LBB0_297:
	v_lshl_add_u32 v160, s54, 8, v156
	v_lshl_or_b32 v144, s38, 8, v158
	v_mov_b64_e32 v[146:147], s[42:43]
	v_ashrrev_i32_e32 v145, 31, v144
	v_mad_i64_i32 v[148:149], s[20:21], v160, s84, v[146:147]
	s_movk_i32 s14, 0x8a0
	v_lshl_add_u64 v[146:147], v[144:145], 1, v[148:149]
	v_cmp_gt_i32_e32 vcc, s14, v144
	s_and_saveexec_b64 s[20:21], vcc
	s_xor_b64 s[20:21], exec, s[20:21]
	s_cbranch_execz .LBB0_299
	v_cvt_pk_bf16_f32 v162, v130, v131
	v_cvt_pk_bf16_f32 v163, v132, v133
	v_cvt_pk_bf16_f32 v164, v126, v127
	v_cvt_pk_bf16_f32 v165, v128, v129
	global_store_dwordx4 v[146:147], v[162:165], off
.LBB0_299:
	s_or_saveexec_b64 s[20:21], s[20:21]
	v_lshl_add_u64 v[148:149], v[148:149], 0, v[144:145]
	s_xor_b64 exec, exec, s[20:21]
	s_cbranch_execz .LBB0_301
	v_mov_b32_e32 v162, v1
	v_mov_b32_e32 v163, v1
	v_cvt_pk_fp8_f32 v162, v130, v131
	v_cvt_pk_fp8_f32 v163, v126, v127
	v_cvt_pk_fp8_f32 v162, v132, v133 op_sel:[0,0,1]
	v_cvt_pk_fp8_f32 v163, v128, v129 op_sel:[0,0,1]
	global_store_dwordx2 v[148:149], v[162:163], off offset:2208
.LBB0_301:
	s_or_b64 exec, exec, s[20:21]
	v_or_b32_e32 v126, 0x80, v144
	v_cmp_gt_i32_e64 s[38:39], s14, v126
	s_and_saveexec_b64 s[20:21], s[38:39]
	s_xor_b64 s[20:21], exec, s[20:21]
	s_cbranch_execz .LBB0_303
	v_cvt_pk_bf16_f32 v126, v122, v123
	v_cvt_pk_bf16_f32 v127, v124, v125
	v_cvt_pk_bf16_f32 v128, v118, v119
	v_cvt_pk_bf16_f32 v129, v120, v121
	global_store_dwordx4 v[146:147], v[126:129], off offset:256
.LBB0_303:
	s_andn2_saveexec_b64 s[20:21], s[20:21]
	s_cbranch_execz .LBB0_305
	v_mov_b32_e32 v126, v1
	v_mov_b32_e32 v127, v1
	v_cvt_pk_fp8_f32 v126, v122, v123
	v_cvt_pk_fp8_f32 v127, v118, v119
	v_cvt_pk_fp8_f32 v126, v124, v125 op_sel:[0,0,1]
	v_cvt_pk_fp8_f32 v127, v120, v121 op_sel:[0,0,1]
	global_store_dwordx2 v[148:149], v[126:127], off offset:2336
.LBB0_305:
	s_or_b64 exec, exec, s[20:21]
	v_or_b32_e32 v120, 16, v160
	v_mov_b64_e32 v[118:119], s[42:43]
	v_mad_i64_i32 v[120:121], s[20:21], v120, s84, v[118:119]
	v_lshl_add_u64 v[118:119], v[144:145], 1, v[120:121]
	s_and_saveexec_b64 s[20:21], vcc
	s_xor_b64 s[20:21], exec, s[20:21]
	s_cbranch_execz .LBB0_309
	v_cvt_pk_bf16_f32 v122, v114, v115
	v_cvt_pk_bf16_f32 v123, v116, v117
	v_cvt_pk_bf16_f32 v124, v110, v111
	v_cvt_pk_bf16_f32 v125, v112, v113
	global_store_dwordx4 v[118:119], v[122:125], off
	s_or_saveexec_b64 s[20:21], s[20:21]
	v_lshl_add_u64 v[120:121], v[120:121], 0, v[144:145]
	s_xor_b64 exec, exec, s[20:21]
	s_cbranch_execnz .LBB0_310

; __device__ __forceinline__ unsigned cvt_pk_bf16(float lo, float hi) { unsigned r; asm volatile("v_cvt_pk_bf16_f32 %0, %1, %2" : "=v"(r) : "v"(lo), "v"(hi)); return r; }
;     __device__ __forceinline__ bool operator()(f32x4 (&acc)[2][2][4][2], const Unit& u, int wr, int wc, int fr, int fq) const {
;     ...
;                 for (int bj = 0; bj < 2; ++bj) { f32x4 v0 = acc[ai][bj][m][0], v1 = acc[ai][bj][m][1]; u32x4 w;
;                     if (col0 + bj * HALF >= OFF_MERGE) {
;                         int lo = __builtin_amdgcn_cvt_pk_fp8_f32(v0[0], v0[1], 0, false); lo = __builtin_amdgcn_cvt_pk_fp8_f32(v0[2], v0[3], lo, true);
;                         int hi = __builtin_amdgcn_cvt_pk_fp8_f32(v1[0], v1[1], 0, false); hi = __builtin_amdgcn_cvt_pk_fp8_f32(v1[2], v1[3], hi, true);
;                         *(u32x2*)((unsigned char*)(O + (size_t)(row0 + ai * HALF + m * 16) * ldc + OFF_MERGE) + (col0 + bj * HALF - OFF_MERGE)) = (u32x2){(unsigned)lo, (unsigned)hi};
;                         continue; }
;                     w.x = cvt_pk_bf16(v0[0], v0[1]); w.y = cvt_pk_bf16(v0[2], v0[3]); w.z = cvt_pk_bf16(v1[0], v1[1]); w.w = cvt_pk_bf16(v1[2], v1[3]);
;                     *(u32x4*)(rowp + bj * HALF) = w; } }
.LBB0_308:
	v_cvt_pk_bf16_f32 v110, v106, v107
	v_cvt_pk_bf16_f32 v111, v108, v109
	v_cvt_pk_bf16_f32 v112, v102, v103
	v_cvt_pk_bf16_f32 v113, v104, v105
	global_store_dwordx4 v[118:119], v[110:113], off offset:256
	s_andn2_saveexec_b64 s[20:21], s[20:21]
	s_cbranch_execnz .LBB0_312
	s_branch .LBB0_313

;     __device__ __forceinline__ bool operator()(f32x4 (&acc)[2][2][4][2], const Unit& u, int wr, int wc, int fr, int fq) const {
;     ...
;                     if (col0 + bj * HALF >= OFF_MERGE) {
;                         int lo = __builtin_amdgcn_cvt_pk_fp8_f32(v0[0], v0[1], 0, false); lo = __builtin_amdgcn_cvt_pk_fp8_f32(v0[2], v0[3], lo, true);
;                         int hi = __builtin_amdgcn_cvt_pk_fp8_f32(v1[0], v1[1], 0, false); hi = __builtin_amdgcn_cvt_pk_fp8_f32(v1[2], v1[3], hi, true);
;                         *(u32x2*)((unsigned char*)(O + (size_t)(row0 + ai * HALF + m * 16) * ldc + OFF_MERGE) + (col0 + bj * HALF - OFF_MERGE)) = (u32x2){(unsigned)lo, (unsigned)hi};
;                         continue; }
.LBB0_310:
	v_mov_b32_e32 v122, v1
	v_mov_b32_e32 v123, v1
	v_cvt_pk_fp8_f32 v122, v114, v115
	v_cvt_pk_fp8_f32 v123, v110, v111
	v_cvt_pk_fp8_f32 v122, v116, v117 op_sel:[0,0,1]
	v_cvt_pk_fp8_f32 v123, v112, v113 op_sel:[0,0,1]
	global_store_dwordx2 v[120:121], v[122:123], off offset:2208
	s_or_b64 exec, exec, s[20:21]
	s_and_saveexec_b64 s[20:21], s[38:39]
	s_xor_b64 s[20:21], exec, s[20:21]
	s_cbranch_execnz .LBB0_308

; __device__ __forceinline__ unsigned cvt_pk_bf16(float lo, float hi) { unsigned r; asm volatile("v_cvt_pk_bf16_f32 %0, %1, %2" : "=v"(r) : "v"(lo), "v"(hi)); return r; }
;     __device__ __forceinline__ bool operator()(f32x4 (&acc)[2][2][4][2], const Unit& u, int wr, int wc, int fr, int fq) const {
;     ...
;                     if (col0 + bj * HALF >= OFF_MERGE) {
;                         int lo = __builtin_amdgcn_cvt_pk_fp8_f32(v0[0], v0[1], 0, false); lo = __builtin_amdgcn_cvt_pk_fp8_f32(v0[2], v0[3], lo, true);
;                         int hi = __builtin_amdgcn_cvt_pk_fp8_f32(v1[0], v1[1], 0, false); hi = __builtin_amdgcn_cvt_pk_fp8_f32(v1[2], v1[3], hi, true);
;                         *(u32x2*)((unsigned char*)(O + (size_t)(row0 + ai * HALF + m * 16) * ldc + OFF_MERGE) + (col0 + bj * HALF - OFF_MERGE)) = (u32x2){(unsigned)lo, (unsigned)hi};
;                         continue; }
;                     w.x = cvt_pk_bf16(v0[0], v0[1]); w.y = cvt_pk_bf16(v0[2], v0[3]); w.z = cvt_pk_bf16(v1[0], v1[1]); w.w = cvt_pk_bf16(v1[2], v1[3]);
;                     *(u32x4*)(rowp + bj * HALF) = w; } }
.LBB0_312:
	v_mov_b32_e32 v110, v1
	v_mov_b32_e32 v111, v1
	v_cvt_pk_fp8_f32 v110, v106, v107
	v_cvt_pk_fp8_f32 v111, v102, v103
	v_cvt_pk_fp8_f32 v110, v108, v109 op_sel:[0,0,1]
	v_cvt_pk_fp8_f32 v111, v104, v105 op_sel:[0,0,1]
	global_store_dwordx2 v[120:121], v[110:111], off offset:2336
.LBB0_313:
	s_or_b64 exec, exec, s[20:21]
	v_or_b32_e32 v104, 32, v160
	v_mov_b64_e32 v[102:103], s[42:43]
	v_mad_i64_i32 v[104:105], s[20:21], v104, s84, v[102:103]
	v_lshl_add_u64 v[102:103], v[144:145], 1, v[104:105]
	s_and_saveexec_b64 s[20:21], vcc
	s_xor_b64 s[20:21], exec, s[20:21]
	s_cbranch_execz .LBB0_317
	v_cvt_pk_bf16_f32 v106, v98, v99
	v_cvt_pk_bf16_f32 v107, v100, v101
	v_cvt_pk_bf16_f32 v108, v94, v95
	v_cvt_pk_bf16_f32 v109, v96, v97
	global_store_dwordx4 v[102:103], v[106:109], off
	s_or_saveexec_b64 s[20:21], s[20:21]
	v_lshl_add_u64 v[104:105], v[104:105], 0, v[144:145]
	s_xor_b64 exec, exec, s[20:21]
	s_cbranch_execnz .LBB0_318

; __device__ __forceinline__ unsigned cvt_pk_bf16(float lo, float hi) { unsigned r; asm volatile("v_cvt_pk_bf16_f32 %0, %1, %2" : "=v"(r) : "v"(lo), "v"(hi)); return r; }
;     __device__ __forceinline__ bool operator()(f32x4 (&acc)[2][2][4][2], const Unit& u, int wr, int wc, int fr, int fq) const {
;     ...
;                 for (int bj = 0; bj < 2; ++bj) { f32x4 v0 = acc[ai][bj][m][0], v1 = acc[ai][bj][m][1]; u32x4 w;
;                     if (col0 + bj * HALF >= OFF_MERGE) {
;                         int lo = __builtin_amdgcn_cvt_pk_fp8_f32(v0[0], v0[1], 0, false); lo = __builtin_amdgcn_cvt_pk_fp8_f32(v0[2], v0[3], lo, true);
;                         int hi = __builtin_amdgcn_cvt_pk_fp8_f32(v1[0], v1[1], 0, false); hi = __builtin_amdgcn_cvt_pk_fp8_f32(v1[2], v1[3], hi, true);
;                         *(u32x2*)((unsigned char*)(O + (size_t)(row0 + ai * HALF + m * 16) * ldc + OFF_MERGE) + (col0 + bj * HALF - OFF_MERGE)) = (u32x2){(unsigned)lo, (unsigned)hi};
;                         continue; }
;                     w.x = cvt_pk_bf16(v0[0], v0[1]); w.y = cvt_pk_bf16(v0[2], v0[3]); w.z = cvt_pk_bf16(v1[0], v1[1]); w.w = cvt_pk_bf16(v1[2], v1[3]);
;                     *(u32x4*)(rowp + bj * HALF) = w; } }
.LBB0_316:
	v_cvt_pk_bf16_f32 v94, v90, v91
	v_cvt_pk_bf16_f32 v95, v92, v93
	v_cvt_pk_bf16_f32 v96, v86, v87
	v_cvt_pk_bf16_f32 v97, v88, v89
	global_store_dwordx4 v[102:103], v[94:97], off offset:256
	s_andn2_saveexec_b64 s[20:21], s[20:21]
	s_cbranch_execnz .LBB0_320
	s_branch .LBB0_321

;     __device__ __forceinline__ bool operator()(f32x4 (&acc)[2][2][4][2], const Unit& u, int wr, int wc, int fr, int fq) const {
;     ...
;                     if (col0 + bj * HALF >= OFF_MERGE) {
;                         int lo = __builtin_amdgcn_cvt_pk_fp8_f32(v0[0], v0[1], 0, false); lo = __builtin_amdgcn_cvt_pk_fp8_f32(v0[2], v0[3], lo, true);
;                         int hi = __builtin_amdgcn_cvt_pk_fp8_f32(v1[0], v1[1], 0, false); hi = __builtin_amdgcn_cvt_pk_fp8_f32(v1[2], v1[3], hi, true);
;                         *(u32x2*)((unsigned char*)(O + (size_t)(row0 + ai * HALF + m * 16) * ldc + OFF_MERGE) + (col0 + bj * HALF - OFF_MERGE)) = (u32x2){(unsigned)lo, (unsigned)hi};
;                         continue; }
.LBB0_318:
	v_mov_b32_e32 v106, v1
	v_mov_b32_e32 v107, v1
	v_cvt_pk_fp8_f32 v106, v98, v99
	v_cvt_pk_fp8_f32 v107, v94, v95
	v_cvt_pk_fp8_f32 v106, v100, v101 op_sel:[0,0,1]
	v_cvt_pk_fp8_f32 v107, v96, v97 op_sel:[0,0,1]
	global_store_dwordx2 v[104:105], v[106:107], off offset:2208
	s_or_b64 exec, exec, s[20:21]
	s_and_saveexec_b64 s[20:21], s[38:39]
	s_xor_b64 s[20:21], exec, s[20:21]
	s_cbranch_execnz .LBB0_316

; __device__ __forceinline__ unsigned cvt_pk_bf16(float lo, float hi) { unsigned r; asm volatile("v_cvt_pk_bf16_f32 %0, %1, %2" : "=v"(r) : "v"(lo), "v"(hi)); return r; }
;     __device__ __forceinline__ bool operator()(f32x4 (&acc)[2][2][4][2], const Unit& u, int wr, int wc, int fr, int fq) const {
;     ...
;                     if (col0 + bj * HALF >= OFF_MERGE) {
;                         int lo = __builtin_amdgcn_cvt_pk_fp8_f32(v0[0], v0[1], 0, false); lo = __builtin_amdgcn_cvt_pk_fp8_f32(v0[2], v0[3], lo, true);
;                         int hi = __builtin_amdgcn_cvt_pk_fp8_f32(v1[0], v1[1], 0, false); hi = __builtin_amdgcn_cvt_pk_fp8_f32(v1[2], v1[3], hi, true);
;                         *(u32x2*)((unsigned char*)(O + (size_t)(row0 + ai * HALF + m * 16) * ldc + OFF_MERGE) + (col0 + bj * HALF - OFF_MERGE)) = (u32x2){(unsigned)lo, (unsigned)hi};
;                         continue; }
;                     w.x = cvt_pk_bf16(v0[0], v0[1]); w.y = cvt_pk_bf16(v0[2], v0[3]); w.z = cvt_pk_bf16(v1[0], v1[1]); w.w = cvt_pk_bf16(v1[2], v1[3]);
;                     *(u32x4*)(rowp + bj * HALF) = w; } }
.LBB0_320:
	v_mov_b32_e32 v94, v1
	v_mov_b32_e32 v95, v1
	v_cvt_pk_fp8_f32 v94, v90, v91
	v_cvt_pk_fp8_f32 v95, v86, v87
	v_cvt_pk_fp8_f32 v94, v92, v93 op_sel:[0,0,1]
	v_cvt_pk_fp8_f32 v95, v88, v89 op_sel:[0,0,1]
	global_store_dwordx2 v[104:105], v[94:95], off offset:2336
.LBB0_321:
	s_or_b64 exec, exec, s[20:21]
	v_or_b32_e32 v88, 48, v160
	v_mov_b64_e32 v[86:87], s[42:43]
	v_mad_i64_i32 v[88:89], s[20:21], v88, s84, v[86:87]
	v_lshl_add_u64 v[86:87], v[144:145], 1, v[88:89]
	s_and_saveexec_b64 s[20:21], vcc
	s_xor_b64 s[20:21], exec, s[20:21]
	s_cbranch_execz .LBB0_325
	v_cvt_pk_bf16_f32 v90, v82, v83
	v_cvt_pk_bf16_f32 v91, v84, v85
	v_cvt_pk_bf16_f32 v92, v78, v79
	v_cvt_pk_bf16_f32 v93, v80, v81
	global_store_dwordx4 v[86:87], v[90:93], off
	s_or_saveexec_b64 s[20:21], s[20:21]
	v_lshl_add_u64 v[88:89], v[88:89], 0, v[144:145]
	s_xor_b64 exec, exec, s[20:21]
	s_cbranch_execnz .LBB0_326

; __device__ __forceinline__ unsigned cvt_pk_bf16(float lo, float hi) { unsigned r; asm volatile("v_cvt_pk_bf16_f32 %0, %1, %2" : "=v"(r) : "v"(lo), "v"(hi)); return r; }
;     __device__ __forceinline__ bool operator()(f32x4 (&acc)[2][2][4][2], const Unit& u, int wr, int wc, int fr, int fq) const {
;     ...
;                 for (int bj = 0; bj < 2; ++bj) { f32x4 v0 = acc[ai][bj][m][0], v1 = acc[ai][bj][m][1]; u32x4 w;
;                     if (col0 + bj * HALF >= OFF_MERGE) {
;                         int lo = __builtin_amdgcn_cvt_pk_fp8_f32(v0[0], v0[1], 0, false); lo = __builtin_amdgcn_cvt_pk_fp8_f32(v0[2], v0[3], lo, true);
;                         int hi = __builtin_amdgcn_cvt_pk_fp8_f32(v1[0], v1[1], 0, false); hi = __builtin_amdgcn_cvt_pk_fp8_f32(v1[2], v1[3], hi, true);
;                         *(u32x2*)((unsigned char*)(O + (size_t)(row0 + ai * HALF + m * 16) * ldc + OFF_MERGE) + (col0 + bj * HALF - OFF_MERGE)) = (u32x2){(unsigned)lo, (unsigned)hi};
;                         continue; }
;                     w.x = cvt_pk_bf16(v0[0], v0[1]); w.y = cvt_pk_bf16(v0[2], v0[3]); w.z = cvt_pk_bf16(v1[0], v1[1]); w.w = cvt_pk_bf16(v1[2], v1[3]);
;                     *(u32x4*)(rowp + bj * HALF) = w; } }
.LBB0_324:
	v_cvt_pk_bf16_f32 v78, v74, v75
	v_cvt_pk_bf16_f32 v79, v76, v77
	v_cvt_pk_bf16_f32 v80, v70, v71
	v_cvt_pk_bf16_f32 v81, v72, v73
	global_store_dwordx4 v[86:87], v[78:81], off offset:256
	s_andn2_saveexec_b64 s[20:21], s[20:21]
	s_cbranch_execnz .LBB0_328
	s_branch .LBB0_329

;     __device__ __forceinline__ bool operator()(f32x4 (&acc)[2][2][4][2], const Unit& u, int wr, int wc, int fr, int fq) const {
;     ...
;                     if (col0 + bj * HALF >= OFF_MERGE) {
;                         int lo = __builtin_amdgcn_cvt_pk_fp8_f32(v0[0], v0[1], 0, false); lo = __builtin_amdgcn_cvt_pk_fp8_f32(v0[2], v0[3], lo, true);
;                         int hi = __builtin_amdgcn_cvt_pk_fp8_f32(v1[0], v1[1], 0, false); hi = __builtin_amdgcn_cvt_pk_fp8_f32(v1[2], v1[3], hi, true);
;                         *(u32x2*)((unsigned char*)(O + (size_t)(row0 + ai * HALF + m * 16) * ldc + OFF_MERGE) + (col0 + bj * HALF - OFF_MERGE)) = (u32x2){(unsigned)lo, (unsigned)hi};
;                         continue; }
.LBB0_326:
	v_mov_b32_e32 v90, v1
	v_mov_b32_e32 v91, v1
	v_cvt_pk_fp8_f32 v90, v82, v83
	v_cvt_pk_fp8_f32 v91, v78, v79
	v_cvt_pk_fp8_f32 v90, v84, v85 op_sel:[0,0,1]
	v_cvt_pk_fp8_f32 v91, v80, v81 op_sel:[0,0,1]
	global_store_dwordx2 v[88:89], v[90:91], off offset:2208
	s_or_b64 exec, exec, s[20:21]
	s_and_saveexec_b64 s[20:21], s[38:39]
	s_xor_b64 s[20:21], exec, s[20:21]
	s_cbranch_execnz .LBB0_324

; __device__ __forceinline__ unsigned cvt_pk_bf16(float lo, float hi) { unsigned r; asm volatile("v_cvt_pk_bf16_f32 %0, %1, %2" : "=v"(r) : "v"(lo), "v"(hi)); return r; }
;     __device__ __forceinline__ bool operator()(f32x4 (&acc)[2][2][4][2], const Unit& u, int wr, int wc, int fr, int fq) const {
;     ...
;                     if (col0 + bj * HALF >= OFF_MERGE) {
;                         int lo = __builtin_amdgcn_cvt_pk_fp8_f32(v0[0], v0[1], 0, false); lo = __builtin_amdgcn_cvt_pk_fp8_f32(v0[2], v0[3], lo, true);
;                         int hi = __builtin_amdgcn_cvt_pk_fp8_f32(v1[0], v1[1], 0, false); hi = __builtin_amdgcn_cvt_pk_fp8_f32(v1[2], v1[3], hi, true);
;                         *(u32x2*)((unsigned char*)(O + (size_t)(row0 + ai * HALF + m * 16) * ldc + OFF_MERGE) + (col0 + bj * HALF - OFF_MERGE)) = (u32x2){(unsigned)lo, (unsigned)hi};
;                         continue; }
;                     w.x = cvt_pk_bf16(v0[0], v0[1]); w.y = cvt_pk_bf16(v0[2], v0[3]); w.z = cvt_pk_bf16(v1[0], v1[1]); w.w = cvt_pk_bf16(v1[2], v1[3]);
;                     *(u32x4*)(rowp + bj * HALF) = w; } }
.LBB0_328:
	v_mov_b32_e32 v78, v1
	v_mov_b32_e32 v79, v1
	v_cvt_pk_fp8_f32 v78, v74, v75
	v_cvt_pk_fp8_f32 v79, v70, v71
	v_cvt_pk_fp8_f32 v78, v76, v77 op_sel:[0,0,1]
	v_cvt_pk_fp8_f32 v79, v72, v73 op_sel:[0,0,1]
	global_store_dwordx2 v[88:89], v[78:79], off offset:2336
.LBB0_329:
	s_or_b64 exec, exec, s[20:21]
	v_add_u32_e32 v72, 0x80, v160
	v_mov_b64_e32 v[70:71], s[42:43]
	v_mad_i64_i32 v[72:73], s[20:21], v72, s84, v[70:71]
	v_lshl_add_u64 v[70:71], v[144:145], 1, v[72:73]
	s_and_saveexec_b64 s[20:21], vcc
	s_xor_b64 s[20:21], exec, s[20:21]
	s_cbranch_execz .LBB0_333
	v_cvt_pk_bf16_f32 v74, v66, v67
	v_cvt_pk_bf16_f32 v75, v68, v69
	v_cvt_pk_bf16_f32 v76, v62, v63
	v_cvt_pk_bf16_f32 v77, v64, v65
	global_store_dwordx4 v[70:71], v[74:77], off
	s_or_saveexec_b64 s[20:21], s[20:21]
	v_lshl_add_u64 v[72:73], v[72:73], 0, v[144:145]
	s_xor_b64 exec, exec, s[20:21]
	s_cbranch_execnz .LBB0_334

; __device__ __forceinline__ unsigned cvt_pk_bf16(float lo, float hi) { unsigned r; asm volatile("v_cvt_pk_bf16_f32 %0, %1, %2" : "=v"(r) : "v"(lo), "v"(hi)); return r; }
;     __device__ __forceinline__ bool operator()(f32x4 (&acc)[2][2][4][2], const Unit& u, int wr, int wc, int fr, int fq) const {
;     ...
;                 for (int bj = 0; bj < 2; ++bj) { f32x4 v0 = acc[ai][bj][m][0], v1 = acc[ai][bj][m][1]; u32x4 w;
;                     if (col0 + bj * HALF >= OFF_MERGE) {
;                         int lo = __builtin_amdgcn_cvt_pk_fp8_f32(v0[0], v0[1], 0, false); lo = __builtin_amdgcn_cvt_pk_fp8_f32(v0[2], v0[3], lo, true);
;                         int hi = __builtin_amdgcn_cvt_pk_fp8_f32(v1[0], v1[1], 0, false); hi = __builtin_amdgcn_cvt_pk_fp8_f32(v1[2], v1[3], hi, true);
;                         *(u32x2*)((unsigned char*)(O + (size_t)(row0 + ai * HALF + m * 16) * ldc + OFF_MERGE) + (col0 + bj * HALF - OFF_MERGE)) = (u32x2){(unsigned)lo, (unsigned)hi};
;                         continue; }
;                     w.x = cvt_pk_bf16(v0[0], v0[1]); w.y = cvt_pk_bf16(v0[2], v0[3]); w.z = cvt_pk_bf16(v1[0], v1[1]); w.w = cvt_pk_bf16(v1[2], v1[3]);
;                     *(u32x4*)(rowp + bj * HALF) = w; } }
.LBB0_332:
	v_cvt_pk_bf16_f32 v62, v58, v59
	v_cvt_pk_bf16_f32 v63, v60, v61
	v_cvt_pk_bf16_f32 v64, v54, v55
	v_cvt_pk_bf16_f32 v65, v56, v57
	global_store_dwordx4 v[70:71], v[62:65], off offset:256
	s_andn2_saveexec_b64 s[20:21], s[20:21]
	s_cbranch_execnz .LBB0_336
	s_branch .LBB0_337

;     __device__ __forceinline__ bool operator()(f32x4 (&acc)[2][2][4][2], const Unit& u, int wr, int wc, int fr, int fq) const {
;     ...
;                     if (col0 + bj * HALF >= OFF_MERGE) {
;                         int lo = __builtin_amdgcn_cvt_pk_fp8_f32(v0[0], v0[1], 0, false); lo = __builtin_amdgcn_cvt_pk_fp8_f32(v0[2], v0[3], lo, true);
;                         int hi = __builtin_amdgcn_cvt_pk_fp8_f32(v1[0], v1[1], 0, false); hi = __builtin_amdgcn_cvt_pk_fp8_f32(v1[2], v1[3], hi, true);
;                         *(u32x2*)((unsigned char*)(O + (size_t)(row0 + ai * HALF + m * 16) * ldc + OFF_MERGE) + (col0 + bj * HALF - OFF_MERGE)) = (u32x2){(unsigned)lo, (unsigned)hi};
;                         continue; }
.LBB0_334:
	v_mov_b32_e32 v74, v1
	v_mov_b32_e32 v75, v1
	v_cvt_pk_fp8_f32 v74, v66, v67
	v_cvt_pk_fp8_f32 v75, v62, v63
	v_cvt_pk_fp8_f32 v74, v68, v69 op_sel:[0,0,1]
	v_cvt_pk_fp8_f32 v75, v64, v65 op_sel:[0,0,1]
	global_store_dwordx2 v[72:73], v[74:75], off offset:2208
	s_or_b64 exec, exec, s[20:21]
	s_and_saveexec_b64 s[20:21], s[38:39]
	s_xor_b64 s[20:21], exec, s[20:21]
	s_cbranch_execnz .LBB0_332

; __device__ __forceinline__ unsigned cvt_pk_bf16(float lo, float hi) { unsigned r; asm volatile("v_cvt_pk_bf16_f32 %0, %1, %2" : "=v"(r) : "v"(lo), "v"(hi)); return r; }
;     __device__ __forceinline__ bool operator()(f32x4 (&acc)[2][2][4][2], const Unit& u, int wr, int wc, int fr, int fq) const {
;     ...
;                     if (col0 + bj * HALF >= OFF_MERGE) {
;                         int lo = __builtin_amdgcn_cvt_pk_fp8_f32(v0[0], v0[1], 0, false); lo = __builtin_amdgcn_cvt_pk_fp8_f32(v0[2], v0[3], lo, true);
;                         int hi = __builtin_amdgcn_cvt_pk_fp8_f32(v1[0], v1[1], 0, false); hi = __builtin_amdgcn_cvt_pk_fp8_f32(v1[2], v1[3], hi, true);
;                         *(u32x2*)((unsigned char*)(O + (size_t)(row0 + ai * HALF + m * 16) * ldc + OFF_MERGE) + (col0 + bj * HALF - OFF_MERGE)) = (u32x2){(unsigned)lo, (unsigned)hi};
;                         continue; }
;                     w.x = cvt_pk_bf16(v0[0], v0[1]); w.y = cvt_pk_bf16(v0[2], v0[3]); w.z = cvt_pk_bf16(v1[0], v1[1]); w.w = cvt_pk_bf16(v1[2], v1[3]);
;                     *(u32x4*)(rowp + bj * HALF) = w; } }
.LBB0_336:
	v_mov_b32_e32 v62, v1
	v_mov_b32_e32 v63, v1
	v_cvt_pk_fp8_f32 v62, v58, v59
	v_cvt_pk_fp8_f32 v63, v54, v55
	v_cvt_pk_fp8_f32 v62, v60, v61 op_sel:[0,0,1]
	v_cvt_pk_fp8_f32 v63, v56, v57 op_sel:[0,0,1]
	global_store_dwordx2 v[72:73], v[62:63], off offset:2336
.LBB0_337:
	s_or_b64 exec, exec, s[20:21]
	v_add_u32_e32 v56, 0x90, v160
	v_mov_b64_e32 v[54:55], s[42:43]
	v_mad_i64_i32 v[56:57], s[20:21], v56, s84, v[54:55]
	v_lshl_add_u64 v[54:55], v[144:145], 1, v[56:57]
	s_and_saveexec_b64 s[20:21], vcc
	s_xor_b64 s[20:21], exec, s[20:21]
	s_cbranch_execz .LBB0_341
	v_cvt_pk_bf16_f32 v58, v50, v51
	v_cvt_pk_bf16_f32 v59, v52, v53
	v_cvt_pk_bf16_f32 v60, v46, v47
	v_cvt_pk_bf16_f32 v61, v48, v49
	global_store_dwordx4 v[54:55], v[58:61], off
	s_or_saveexec_b64 s[20:21], s[20:21]
	v_lshl_add_u64 v[56:57], v[56:57], 0, v[144:145]
	s_xor_b64 exec, exec, s[20:21]
	s_cbranch_execnz .LBB0_342

; __device__ __forceinline__ unsigned cvt_pk_bf16(float lo, float hi) { unsigned r; asm volatile("v_cvt_pk_bf16_f32 %0, %1, %2" : "=v"(r) : "v"(lo), "v"(hi)); return r; }
;     __device__ __forceinline__ bool operator()(f32x4 (&acc)[2][2][4][2], const Unit& u, int wr, int wc, int fr, int fq) const {
;     ...
;                 for (int bj = 0; bj < 2; ++bj) { f32x4 v0 = acc[ai][bj][m][0], v1 = acc[ai][bj][m][1]; u32x4 w;
;                     if (col0 + bj * HALF >= OFF_MERGE) {
;                         int lo = __builtin_amdgcn_cvt_pk_fp8_f32(v0[0], v0[1], 0, false); lo = __builtin_amdgcn_cvt_pk_fp8_f32(v0[2], v0[3], lo, true);
;                         int hi = __builtin_amdgcn_cvt_pk_fp8_f32(v1[0], v1[1], 0, false); hi = __builtin_amdgcn_cvt_pk_fp8_f32(v1[2], v1[3], hi, true);
;                         *(u32x2*)((unsigned char*)(O + (size_t)(row0 + ai * HALF + m * 16) * ldc + OFF_MERGE) + (col0 + bj * HALF - OFF_MERGE)) = (u32x2){(unsigned)lo, (unsigned)hi};
;                         continue; }
;                     w.x = cvt_pk_bf16(v0[0], v0[1]); w.y = cvt_pk_bf16(v0[2], v0[3]); w.z = cvt_pk_bf16(v1[0], v1[1]); w.w = cvt_pk_bf16(v1[2], v1[3]);
;                     *(u32x4*)(rowp + bj * HALF) = w; } }
.LBB0_340:
	v_cvt_pk_bf16_f32 v46, v42, v43
	v_cvt_pk_bf16_f32 v47, v44, v45
	v_cvt_pk_bf16_f32 v48, v38, v39
	v_cvt_pk_bf16_f32 v49, v40, v41
	global_store_dwordx4 v[54:55], v[46:49], off offset:256
	s_andn2_saveexec_b64 s[20:21], s[20:21]
	s_cbranch_execnz .LBB0_344
	s_branch .LBB0_345

;     __device__ __forceinline__ bool operator()(f32x4 (&acc)[2][2][4][2], const Unit& u, int wr, int wc, int fr, int fq) const {
;     ...
;                     if (col0 + bj * HALF >= OFF_MERGE) {
;                         int lo = __builtin_amdgcn_cvt_pk_fp8_f32(v0[0], v0[1], 0, false); lo = __builtin_amdgcn_cvt_pk_fp8_f32(v0[2], v0[3], lo, true);
;                         int hi = __builtin_amdgcn_cvt_pk_fp8_f32(v1[0], v1[1], 0, false); hi = __builtin_amdgcn_cvt_pk_fp8_f32(v1[2], v1[3], hi, true);
;                         *(u32x2*)((unsigned char*)(O + (size_t)(row0 + ai * HALF + m * 16) * ldc + OFF_MERGE) + (col0 + bj * HALF - OFF_MERGE)) = (u32x2){(unsigned)lo, (unsigned)hi};
;                         continue; }
.LBB0_342:
	v_mov_b32_e32 v58, v1
	v_mov_b32_e32 v59, v1
	v_cvt_pk_fp8_f32 v58, v50, v51
	v_cvt_pk_fp8_f32 v59, v46, v47
	v_cvt_pk_fp8_f32 v58, v52, v53 op_sel:[0,0,1]
	v_cvt_pk_fp8_f32 v59, v48, v49 op_sel:[0,0,1]
	global_store_dwordx2 v[56:57], v[58:59], off offset:2208
	s_or_b64 exec, exec, s[20:21]
	s_and_saveexec_b64 s[20:21], s[38:39]
	s_xor_b64 s[20:21], exec, s[20:21]
	s_cbranch_execnz .LBB0_340

; __device__ __forceinline__ unsigned cvt_pk_bf16(float lo, float hi) { unsigned r; asm volatile("v_cvt_pk_bf16_f32 %0, %1, %2" : "=v"(r) : "v"(lo), "v"(hi)); return r; }
;     __device__ __forceinline__ bool operator()(f32x4 (&acc)[2][2][4][2], const Unit& u, int wr, int wc, int fr, int fq) const {
;     ...
;                     if (col0 + bj * HALF >= OFF_MERGE) {
;                         int lo = __builtin_amdgcn_cvt_pk_fp8_f32(v0[0], v0[1], 0, false); lo = __builtin_amdgcn_cvt_pk_fp8_f32(v0[2], v0[3], lo, true);
;                         int hi = __builtin_amdgcn_cvt_pk_fp8_f32(v1[0], v1[1], 0, false); hi = __builtin_amdgcn_cvt_pk_fp8_f32(v1[2], v1[3], hi, true);
;                         *(u32x2*)((unsigned char*)(O + (size_t)(row0 + ai * HALF + m * 16) * ldc + OFF_MERGE) + (col0 + bj * HALF - OFF_MERGE)) = (u32x2){(unsigned)lo, (unsigned)hi};
;                         continue; }
;                     w.x = cvt_pk_bf16(v0[0], v0[1]); w.y = cvt_pk_bf16(v0[2], v0[3]); w.z = cvt_pk_bf16(v1[0], v1[1]); w.w = cvt_pk_bf16(v1[2], v1[3]);
;                     *(u32x4*)(rowp + bj * HALF) = w; } }
.LBB0_344:
	v_mov_b32_e32 v46, v1
	v_mov_b32_e32 v47, v1
	v_cvt_pk_fp8_f32 v46, v42, v43
	v_cvt_pk_fp8_f32 v47, v38, v39
	v_cvt_pk_fp8_f32 v46, v44, v45 op_sel:[0,0,1]
	v_cvt_pk_fp8_f32 v47, v40, v41 op_sel:[0,0,1]
	global_store_dwordx2 v[56:57], v[46:47], off offset:2336
.LBB0_345:
	s_or_b64 exec, exec, s[20:21]
	v_add_u32_e32 v40, 0xa0, v160
	v_mov_b64_e32 v[38:39], s[42:43]
	v_mad_i64_i32 v[40:41], s[20:21], v40, s84, v[38:39]
	v_lshl_add_u64 v[38:39], v[144:145], 1, v[40:41]
	s_and_saveexec_b64 s[20:21], vcc
	s_xor_b64 s[20:21], exec, s[20:21]
	s_cbranch_execz .LBB0_349
	v_cvt_pk_bf16_f32 v42, v34, v35
	v_cvt_pk_bf16_f32 v43, v36, v37
	v_cvt_pk_bf16_f32 v44, v30, v31
	v_cvt_pk_bf16_f32 v45, v32, v33
	global_store_dwordx4 v[38:39], v[42:45], off
	s_or_saveexec_b64 s[20:21], s[20:21]
	v_lshl_add_u64 v[40:41], v[40:41], 0, v[144:145]
	s_xor_b64 exec, exec, s[20:21]
	s_cbranch_execnz .LBB0_350

; __device__ __forceinline__ unsigned cvt_pk_bf16(float lo, float hi) { unsigned r; asm volatile("v_cvt_pk_bf16_f32 %0, %1, %2" : "=v"(r) : "v"(lo), "v"(hi)); return r; }
;     __device__ __forceinline__ bool operator()(f32x4 (&acc)[2][2][4][2], const Unit& u, int wr, int wc, int fr, int fq) const {
;     ...
;                 for (int bj = 0; bj < 2; ++bj) { f32x4 v0 = acc[ai][bj][m][0], v1 = acc[ai][bj][m][1]; u32x4 w;
;                     if (col0 + bj * HALF >= OFF_MERGE) {
;                         int lo = __builtin_amdgcn_cvt_pk_fp8_f32(v0[0], v0[1], 0, false); lo = __builtin_amdgcn_cvt_pk_fp8_f32(v0[2], v0[3], lo, true);
;                         int hi = __builtin_amdgcn_cvt_pk_fp8_f32(v1[0], v1[1], 0, false); hi = __builtin_amdgcn_cvt_pk_fp8_f32(v1[2], v1[3], hi, true);
;                         *(u32x2*)((unsigned char*)(O + (size_t)(row0 + ai * HALF + m * 16) * ldc + OFF_MERGE) + (col0 + bj * HALF - OFF_MERGE)) = (u32x2){(unsigned)lo, (unsigned)hi};
;                         continue; }
;                     w.x = cvt_pk_bf16(v0[0], v0[1]); w.y = cvt_pk_bf16(v0[2], v0[3]); w.z = cvt_pk_bf16(v1[0], v1[1]); w.w = cvt_pk_bf16(v1[2], v1[3]);
;                     *(u32x4*)(rowp + bj * HALF) = w; } }
.LBB0_348:
	v_cvt_pk_bf16_f32 v30, v26, v27
	v_cvt_pk_bf16_f32 v31, v28, v29
	v_cvt_pk_bf16_f32 v32, v22, v23
	v_cvt_pk_bf16_f32 v33, v24, v25
	global_store_dwordx4 v[38:39], v[30:33], off offset:256
	s_andn2_saveexec_b64 s[20:21], s[20:21]
	s_cbranch_execnz .LBB0_352
	s_branch .LBB0_353

;     __device__ __forceinline__ bool operator()(f32x4 (&acc)[2][2][4][2], const Unit& u, int wr, int wc, int fr, int fq) const {
;     ...
;                     if (col0 + bj * HALF >= OFF_MERGE) {
;                         int lo = __builtin_amdgcn_cvt_pk_fp8_f32(v0[0], v0[1], 0, false); lo = __builtin_amdgcn_cvt_pk_fp8_f32(v0[2], v0[3], lo, true);
;                         int hi = __builtin_amdgcn_cvt_pk_fp8_f32(v1[0], v1[1], 0, false); hi = __builtin_amdgcn_cvt_pk_fp8_f32(v1[2], v1[3], hi, true);
;                         *(u32x2*)((unsigned char*)(O + (size_t)(row0 + ai * HALF + m * 16) * ldc + OFF_MERGE) + (col0 + bj * HALF - OFF_MERGE)) = (u32x2){(unsigned)lo, (unsigned)hi};
;                         continue; }
.LBB0_350:
	v_mov_b32_e32 v42, v1
	v_mov_b32_e32 v43, v1
	v_cvt_pk_fp8_f32 v42, v34, v35
	v_cvt_pk_fp8_f32 v43, v30, v31
	v_cvt_pk_fp8_f32 v42, v36, v37 op_sel:[0,0,1]
	v_cvt_pk_fp8_f32 v43, v32, v33 op_sel:[0,0,1]
	global_store_dwordx2 v[40:41], v[42:43], off offset:2208
	s_or_b64 exec, exec, s[20:21]
	s_and_saveexec_b64 s[20:21], s[38:39]
	s_xor_b64 s[20:21], exec, s[20:21]
	s_cbranch_execnz .LBB0_348

; __device__ __forceinline__ unsigned cvt_pk_bf16(float lo, float hi) { unsigned r; asm volatile("v_cvt_pk_bf16_f32 %0, %1, %2" : "=v"(r) : "v"(lo), "v"(hi)); return r; }
;     __device__ __forceinline__ bool operator()(f32x4 (&acc)[2][2][4][2], const Unit& u, int wr, int wc, int fr, int fq) const {
;     ...
;                     if (col0 + bj * HALF >= OFF_MERGE) {
;                         int lo = __builtin_amdgcn_cvt_pk_fp8_f32(v0[0], v0[1], 0, false); lo = __builtin_amdgcn_cvt_pk_fp8_f32(v0[2], v0[3], lo, true);
;                         int hi = __builtin_amdgcn_cvt_pk_fp8_f32(v1[0], v1[1], 0, false); hi = __builtin_amdgcn_cvt_pk_fp8_f32(v1[2], v1[3], hi, true);
;                         *(u32x2*)((unsigned char*)(O + (size_t)(row0 + ai * HALF + m * 16) * ldc + OFF_MERGE) + (col0 + bj * HALF - OFF_MERGE)) = (u32x2){(unsigned)lo, (unsigned)hi};
;                         continue; }
;                     w.x = cvt_pk_bf16(v0[0], v0[1]); w.y = cvt_pk_bf16(v0[2], v0[3]); w.z = cvt_pk_bf16(v1[0], v1[1]); w.w = cvt_pk_bf16(v1[2], v1[3]);
;                     *(u32x4*)(rowp + bj * HALF) = w; } }
.LBB0_352:
	v_mov_b32_e32 v30, v1
	v_mov_b32_e32 v31, v1
	v_cvt_pk_fp8_f32 v30, v26, v27
	v_cvt_pk_fp8_f32 v31, v22, v23
	v_cvt_pk_fp8_f32 v30, v28, v29 op_sel:[0,0,1]
	v_cvt_pk_fp8_f32 v31, v24, v25 op_sel:[0,0,1]
	global_store_dwordx2 v[40:41], v[30:31], off offset:2336
.LBB0_353:
	s_or_b64 exec, exec, s[20:21]
	v_add_u32_e32 v24, 0xb0, v160
	v_mov_b64_e32 v[22:23], s[42:43]
	v_mad_i64_i32 v[24:25], s[20:21], v24, s84, v[22:23]
	v_lshl_add_u64 v[22:23], v[144:145], 1, v[24:25]
	s_and_saveexec_b64 s[20:21], vcc
	s_xor_b64 s[20:21], exec, s[20:21]
	s_cbranch_execz .LBB0_358
	v_cvt_pk_bf16_f32 v26, v18, v19
	v_cvt_pk_bf16_f32 v27, v20, v21
	v_cvt_pk_bf16_f32 v28, v14, v15
	v_cvt_pk_bf16_f32 v29, v16, v17
	global_store_dwordx4 v[22:23], v[26:29], off
	s_or_saveexec_b64 s[20:21], s[20:21]
	v_lshl_add_u64 v[24:25], v[24:25], 0, v[144:145]
	s_xor_b64 exec, exec, s[20:21]
	s_cbranch_execnz .LBB0_359

; __device__ __forceinline__ unsigned cvt_pk_bf16(float lo, float hi) { unsigned r; asm volatile("v_cvt_pk_bf16_f32 %0, %1, %2" : "=v"(r) : "v"(lo), "v"(hi)); return r; }
;     __device__ __forceinline__ bool operator()(f32x4 (&acc)[2][2][4][2], const Unit& u, int wr, int wc, int fr, int fq) const {
;     ...
;                 for (int bj = 0; bj < 2; ++bj) { f32x4 v0 = acc[ai][bj][m][0], v1 = acc[ai][bj][m][1]; u32x4 w;
;                     if (col0 + bj * HALF >= OFF_MERGE) {
;                         int lo = __builtin_amdgcn_cvt_pk_fp8_f32(v0[0], v0[1], 0, false); lo = __builtin_amdgcn_cvt_pk_fp8_f32(v0[2], v0[3], lo, true);
;                         int hi = __builtin_amdgcn_cvt_pk_fp8_f32(v1[0], v1[1], 0, false); hi = __builtin_amdgcn_cvt_pk_fp8_f32(v1[2], v1[3], hi, true);
;                         *(u32x2*)((unsigned char*)(O + (size_t)(row0 + ai * HALF + m * 16) * ldc + OFF_MERGE) + (col0 + bj * HALF - OFF_MERGE)) = (u32x2){(unsigned)lo, (unsigned)hi};
;                         continue; }
;                     w.x = cvt_pk_bf16(v0[0], v0[1]); w.y = cvt_pk_bf16(v0[2], v0[3]); w.z = cvt_pk_bf16(v1[0], v1[1]); w.w = cvt_pk_bf16(v1[2], v1[3]);
;                     *(u32x4*)(rowp + bj * HALF) = w; } }
.LBB0_356:
	v_cvt_pk_bf16_f32 v14, v6, v7
	v_cvt_pk_bf16_f32 v15, v8, v9
	v_cvt_pk_bf16_f32 v16, v2, v3
	v_cvt_pk_bf16_f32 v17, v4, v5
	global_store_dwordx4 v[22:23], v[14:17], off offset:256
	s_andn2_saveexec_b64 s[20:21], s[20:21]
	s_cbranch_execnz .LBB0_361

;     __device__ __forceinline__ bool operator()(f32x4 (&acc)[2][2][4][2], const Unit& u, int wr, int wc, int fr, int fq) const {
;     ...
;                     if (col0 + bj * HALF >= OFF_MERGE) {
;                         int lo = __builtin_amdgcn_cvt_pk_fp8_f32(v0[0], v0[1], 0, false); lo = __builtin_amdgcn_cvt_pk_fp8_f32(v0[2], v0[3], lo, true);
;                         int hi = __builtin_amdgcn_cvt_pk_fp8_f32(v1[0], v1[1], 0, false); hi = __builtin_amdgcn_cvt_pk_fp8_f32(v1[2], v1[3], hi, true);
;                         *(u32x2*)((unsigned char*)(O + (size_t)(row0 + ai * HALF + m * 16) * ldc + OFF_MERGE) + (col0 + bj * HALF - OFF_MERGE)) = (u32x2){(unsigned)lo, (unsigned)hi};
;                         continue; }
.LBB0_359:
	v_mov_b32_e32 v26, v1
	v_mov_b32_e32 v27, v1
	v_cvt_pk_fp8_f32 v26, v18, v19
	v_cvt_pk_fp8_f32 v27, v14, v15
	v_cvt_pk_fp8_f32 v26, v20, v21 op_sel:[0,0,1]
	v_cvt_pk_fp8_f32 v27, v16, v17 op_sel:[0,0,1]
	global_store_dwordx2 v[24:25], v[26:27], off offset:2208
	s_or_b64 exec, exec, s[20:21]
	s_and_saveexec_b64 s[20:21], s[38:39]
	s_xor_b64 s[20:21], exec, s[20:21]
	s_cbranch_execnz .LBB0_356

; __device__ __forceinline__ unsigned cvt_pk_bf16(float lo, float hi) { unsigned r; asm volatile("v_cvt_pk_bf16_f32 %0, %1, %2" : "=v"(r) : "v"(lo), "v"(hi)); return r; }
; template <class Epi>
; __device__ __forceinline__ void gemm_phase(LAS unsigned char* lds, const Gemm g, const Sched& S, const Epi& E) {
;     ...
;         if (!has_next) break;
;     __device__ __forceinline__ bool operator()(f32x4 (&acc)[2][2][4][2], const Unit& u, int wr, int wc, int fr, int fq) const {
;     ...
;                     if (col0 + bj * HALF >= OFF_MERGE) {
;                         int lo = __builtin_amdgcn_cvt_pk_fp8_f32(v0[0], v0[1], 0, false); lo = __builtin_amdgcn_cvt_pk_fp8_f32(v0[2], v0[3], lo, true);
;                         int hi = __builtin_amdgcn_cvt_pk_fp8_f32(v1[0], v1[1], 0, false); hi = __builtin_amdgcn_cvt_pk_fp8_f32(v1[2], v1[3], hi, true);
;                         *(u32x2*)((unsigned char*)(O + (size_t)(row0 + ai * HALF + m * 16) * ldc + OFF_MERGE) + (col0 + bj * HALF - OFF_MERGE)) = (u32x2){(unsigned)lo, (unsigned)hi};
;                         continue; }
;                     w.x = cvt_pk_bf16(v0[0], v0[1]); w.y = cvt_pk_bf16(v0[2], v0[3]); w.z = cvt_pk_bf16(v1[0], v1[1]); w.w = cvt_pk_bf16(v1[2], v1[3]);
;                     *(u32x4*)(rowp + bj * HALF) = w; } }
;         return false;
.LBB0_361:
	v_mov_b32_e32 v14, v1
	v_mov_b32_e32 v15, v1
	v_cvt_pk_fp8_f32 v14, v6, v7
	v_cvt_pk_fp8_f32 v15, v2, v3
	v_cvt_pk_fp8_f32 v14, v8, v9 op_sel:[0,0,1]
	v_cvt_pk_fp8_f32 v15, v4, v5 op_sel:[0,0,1]
	global_store_dwordx2 v[24:25], v[14:15], off offset:2336
	s_or_b64 exec, exec, s[20:21]
	s_andn2_b64 vcc, exec, s[36:37]
	s_mov_b64 s[20:21], -1
	s_cbranch_vccnz .LBB0_287

; __device__ __forceinline__ unsigned cvt_pk_bf16(float lo, float hi) { unsigned r; asm volatile("v_cvt_pk_bf16_f32 %0, %1, %2" : "=v"(r) : "v"(lo), "v"(hi)); return r; }
; __global__ void __launch_bounds__(512, 2) fwd_kernel(KArgs a) {
;     ...
;                 for (int t = gt; t < 2 * 16 * 256 * 64; t += NGT) {
;                     const int kc = t & 63, n = (t >> 6) & 255, g = (t >> 14) & 15, ll = t >> 18;
;                     const int d = n >> 7, ri = (n >> 6) & 1, p = n & 63, k0 = kc * 8, sp = k0 >> 4, j0 = k0 & 15, e = d == 0 ? 31 - sp : sp;
;                     const float* pw = POW + ((size_t)(((ll * 2 + d) * 16 + g) * 33 + e) * 64 + p) * 2; const float pr = pw[0], pi = pw[1];
;                     const float* bb = BBAR + (((size_t)((ll * 2 + d) * 16 + g) * 64 + p) * 16 + j0) * 2; float v[8];
; #pragma unroll
;                     for (int j = 0; j < 8; ++j) { const float br = bb[2 * j], bi = bb[2 * j + 1]; v[j] = ri == 0 ? pr * br - pi * bi : pr * bi + pi * br; }
;                     u32x4 o; o.x = cvt_pk_bf16(v[0], v[1]); o.y = cvt_pk_bf16(v[2], v[3]); o.z = cvt_pk_bf16(v[4], v[5]); o.w = cvt_pk_bf16(v[6], v[7]);
;                     *(u32x4*)(WEND + ((size_t)(ll * 16 + g) * 256 + n) * 512 + k0) = o;
;                 }
.Lmy_exp_145:
	v_bfe_u32 v65, v64, 6, 8
	v_ashrrev_i32_e32 v85, 18, v64
	v_bfe_u32 v67, v61, 4, 5
	v_lshrrev_b32_e32 v62, 9, v64
	v_bfe_u32 v84, v64, 14, 4
	v_bfe_u32 v66, v64, 6, 6
	v_xor_b32_e32 v68, 31, v67
	v_lshlrev_b32_e32 v69, 5, v85
	v_and_b32_e32 v71, 16, v62
	v_cmp_gt_u32_e32 vcc, s48, v65
	v_lshlrev_b32_e32 v62, 3, v66
	v_lshlrev_b32_e32 v72, 4, v66
	v_cndmask_b32_e32 v67, v67, v68, vcc
	v_or3_b32 v66, v69, v71, v84
	v_mad_i32_i24 v68, v66, 33, v67
	v_ashrrev_i32_e32 v67, 31, v66
	v_ashrrev_i32_e32 v69, 31, v68
	v_and_b32_e32 v70, 8, v61
	v_lshlrev_b64 v[66:67], 10, v[66:67]
	v_lshlrev_b64 v[68:69], 9, v[68:69]
	v_or3_b32 v66, v66, v72, v70
	v_lshl_add_u64 v[68:69], s[40:41], 0, v[68:69]
	v_lshl_add_u64 v[78:79], v[66:67], 3, s[42:43]
	v_lshl_add_u64 v[80:81], v[68:69], 0, v[62:63]
	global_load_dwordx4 v[66:69], v[78:79], off offset:16
	global_load_dwordx4 v[70:73], v[78:79], off offset:32
	global_load_dwordx4 v[74:77], v[78:79], off offset:48
	global_load_dwordx2 v[82:83], v[80:81], off
	s_nop 0
	global_load_dwordx4 v[78:81], v[78:79], off
	v_lshl_or_b32 v84, v85, 4, v84
	v_ashrrev_i32_e32 v85, 31, v84
	v_and_b32_e32 v102, 0x1000, v64
	v_add_u32_e32 v64, s46, v64
	v_lshlrev_b64 v[84:85], 18, v[84:85]
	v_and_b32_e32 v86, 0x1f8, v61
	v_cmp_lt_i32_e32 vcc, s56, v64
	v_lshl_add_u64 v[84:85], s[52:53], 0, v[84:85]
	v_lshlrev_b32_e32 v62, 10, v65
	s_or_b64 s[54:55], vcc, s[54:55]
	v_lshl_add_u64 v[84:85], v[84:85], 0, v[62:63]
	v_lshlrev_b32_e32 v62, 1, v86
	v_cmp_eq_u32_e32 vcc, 0, v102
	v_add_u32_e32 v61, s45, v61
	v_lshl_add_u64 v[84:85], v[84:85], 0, v[62:63]
	s_waitcnt vmcnt(0) lgkmcnt(0)
	v_pk_mul_f32 v[90:91], v[82:83], v[66:67]
	v_pk_mul_f32 v[66:67], v[82:83], v[66:67] op_sel:[1,0] op_sel_hi:[0,1]
	v_pk_mul_f32 v[92:93], v[82:83], v[68:69]
	v_pk_mul_f32 v[68:69], v[82:83], v[68:69] op_sel:[1,0] op_sel_hi:[0,1]
	v_pk_mul_f32 v[94:95], v[82:83], v[70:71]
	v_pk_mul_f32 v[70:71], v[82:83], v[70:71] op_sel:[1,0] op_sel_hi:[0,1]
	v_pk_mul_f32 v[96:97], v[82:83], v[72:73]
	v_pk_mul_f32 v[72:73], v[82:83], v[72:73] op_sel:[1,0] op_sel_hi:[0,1]
	v_pk_mul_f32 v[86:87], v[82:83], v[78:79]
	v_pk_mul_f32 v[78:79], v[82:83], v[78:79] op_sel:[1,0] op_sel_hi:[0,1]
	v_pk_mul_f32 v[88:89], v[82:83], v[80:81]
	v_pk_mul_f32 v[80:81], v[82:83], v[80:81] op_sel:[1,0] op_sel_hi:[0,1]
	v_pk_mul_f32 v[98:99], v[82:83], v[74:75]
	v_pk_mul_f32 v[74:75], v[82:83], v[74:75] op_sel:[1,0] op_sel_hi:[0,1]
	v_pk_mul_f32 v[100:101], v[82:83], v[76:77]
	v_pk_mul_f32 v[76:77], v[82:83], v[76:77] op_sel:[1,0] op_sel_hi:[0,1]
	v_add_f32_e32 v66, v66, v67
	v_sub_f32_e32 v67, v92, v93
	v_add_f32_e32 v68, v68, v69
	v_sub_f32_e32 v69, v94, v95
	v_add_f32_e32 v70, v70, v71
	v_sub_f32_e32 v71, v96, v97
	v_add_f32_e32 v72, v72, v73
	v_sub_f32_e32 v62, v86, v87
	v_add_f32_e32 v65, v78, v79
	v_sub_f32_e32 v78, v88, v89
	v_add_f32_e32 v79, v80, v81
	v_sub_f32_e32 v80, v90, v91
	v_sub_f32_e32 v73, v98, v99
	v_add_f32_e32 v74, v74, v75
	v_sub_f32_e32 v75, v100, v101
	v_add_f32_e32 v76, v76, v77
	v_cndmask_b32_e32 v67, v68, v67, vcc
	v_cndmask_b32_e32 v68, v70, v69, vcc
	v_cndmask_b32_e32 v69, v72, v71, vcc
	v_cndmask_b32_e32 v62, v65, v62, vcc
	v_cndmask_b32_e32 v65, v79, v78, vcc
	v_cndmask_b32_e32 v77, v66, v80, vcc
	v_cndmask_b32_e32 v70, v74, v73, vcc
	v_cndmask_b32_e32 v71, v76, v75, vcc
	v_cvt_pk_bf16_f32 v66, v62, v65
	v_cvt_pk_bf16_f32 v67, v77, v67
	v_cvt_pk_bf16_f32 v68, v68, v69
	v_cvt_pk_bf16_f32 v69, v70, v71
	global_store_dwordx4 v[84:85], v[66:69], off
	s_andn2_b64 exec, exec, s[54:55]
	s_cbranch_execnz .Lmy_exp_145

; __device__ __forceinline__ unsigned cvt_pk_bf16(float lo, float hi) { unsigned r; asm volatile("v_cvt_pk_bf16_f32 %0, %1, %2" : "=v"(r) : "v"(lo), "v"(hi)); return r; }
; __global__ void __launch_bounds__(512, 2) fwd_kernel(KArgs a) {
;     ...
;                 for (int t = gt; t < 2 * 16 * 512 * 96; t += NGT) {
;                     const int kc = t % 96, n = (t / 96) & 511, g = (t / (96 * 512)) & 15, ll = t / (96 * 512 * 16);
;                     const int s = n >> 4, i = n & 15, k0 = kc * 8; float v[8];
;                     if (k0 < 512) { const int sp = k0 >> 4, j0 = k0 & 15;
;                         const float* kf = KT + ((size_t)((ll * 16 + g) * 2 + 0) * 32) * 256 + i * 16 + j0; const float* kb = KT + ((size_t)((ll * 16 + g) * 2 + 1) * 32) * 256 + i * 16 + j0;
; #pragma unroll
;                         for (int j = 0; j < 8; ++j) v[j] = sp < s ? kf[(size_t)(s - sp) * 256 + j] : (sp > s ? kb[(size_t)(sp - s) * 256 + j] : kf[j] + kb[j]);
;                     } else { const int kk = k0 - 512, d = kk >> 7, ri = (kk >> 6) & 1, p0 = kk & 63, e = d == 0 ? s + 1 : 32 - s;
;                         const float* pw = POW + ((size_t)(((ll * 2 + d) * 16 + g) * 33 + e) * 64 + p0) * 2;
;                         const size_t ic = ((size_t)((ll * 2 + d) * 16 + g) * 16 + i) * 64 + p0;
; #pragma unroll
;                         for (int j = 0; j < 8; ++j) { const float cr = a.in[19][ic + j], ci = a.in[20][ic + j], pr = pw[2 * j], pi = pw[2 * j + 1];
;                             v[j] = ri == 0 ? cr * pr - ci * pi : -(cr * pi + ci * pr); }
;                     }
;                     u32x4 o; o.x = cvt_pk_bf16(v[0], v[1]); o.y = cvt_pk_bf16(v[2], v[3]); o.z = cvt_pk_bf16(v[4], v[5]); o.w = cvt_pk_bf16(v[6], v[7]);
;                     *(u32x4*)(BM2 + ((size_t)(ll * 16 + g) * 512 + n) * 768 + k0) = o;
;                 }
.Lmy_exp_149:
	s_or_b64 exec, exec, s[56:57]
	v_and_b32_e32 v64, 0x1ff, v76
	v_lshlrev_b32_e32 v61, 9, v61
	v_lshlrev_b32_e32 v63, 13, v63
	v_or3_b32 v61, v63, v61, v64
	v_mov_b64_e32 v[72:73], s[52:53]
	v_add_u32_e32 v60, s46, v60
	s_waitcnt vmcnt(0) lgkmcnt(0)
	v_cvt_pk_bf16_f32 v68, v67, v77
	v_mad_i64_i32 v[72:73], s[36:37], v61, s51, v[72:73]
	v_ashrrev_i32_e32 v67, 31, v66
	v_cmp_lt_i32_e32 vcc, s61, v60
	v_lshl_add_u64 v[66:67], v[66:67], 1, v[72:73]
	s_or_b64 s[54:55], vcc, s[54:55]
	v_add_u32_e32 v62, s45, v62
	v_cvt_pk_bf16_f32 v69, v78, v79
	v_cvt_pk_bf16_f32 v70, v80, v81
	v_cvt_pk_bf16_f32 v71, v82, v83
	global_store_dwordx4 v[66:67], v[68:71], off
	s_andn2_b64 exec, exec, s[54:55]
	s_cbranch_execz .Lmy_exp_217
.Lmy_exp_150:
	s_mov_b32 s36, 0x2aaaaaab
	v_mul_hi_i32 v63, v60, s36
	v_ashrrev_i32_e32 v61, 4, v63
	v_lshrrev_b32_e32 v64, 31, v63
	v_add_u32_e32 v76, v61, v64
	s_movk_i32 s36, 0xffa0
	v_mad_u64_u32 v[68:69], s[36:37], v76, s36, v[60:61]
	v_lshrrev_b32_e32 v61, 13, v63
	v_ashrrev_i32_e32 v63, 17, v63
	v_add_u32_e32 v61, v61, v64
	v_add_u32_e32 v63, v63, v64
	v_and_b32_e32 v64, 15, v76
	s_movk_i32 s36, 0xfd00
	v_and_b32_e32 v61, 15, v61
	v_bfe_u32 v74, v76, 4, 5
	v_mad_u64_u32 v[66:67], s[36:37], v76, s36, v[62:63]
	v_cmp_lt_i32_e32 vcc, 63, v68
	v_lshlrev_b32_e32 v64, 6, v64
	s_and_saveexec_b64 s[36:37], vcc
	s_xor_b64 s[36:37], exec, s[36:37]
	s_cbranch_execz .Lmy_exp_152
	v_add_u32_e32 v67, 0xfffffe00, v66
	v_cmp_gt_u32_e32 vcc, s48, v67
	v_lshrrev_b32_e32 v67, 3, v67
	v_and_b32_e32 v67, 0x1ffffff0, v67
	v_add_u32_e32 v70, 1, v74
	v_sub_u32_e32 v71, 32, v74
	v_lshl_add_u32 v67, v63, 5, v67
	v_cndmask_b32_e32 v70, v71, v70, vcc
	v_or_b32_e32 v72, v67, v61
	v_mad_u64_u32 v[70:71], s[56:57], v72, 33, v[70:71]
	v_ashrrev_i32_e32 v71, 31, v70
	v_and_b32_e32 v69, 56, v66
	v_lshlrev_b64 v[70:71], 9, v[70:71]
	v_ashrrev_i32_e32 v73, 31, v72
	v_lshl_add_u64 v[70:71], s[40:41], 0, v[70:71]
	v_lshlrev_b32_e32 v74, 3, v69
	v_mov_b32_e32 v75, v65
	v_lshlrev_b64 v[78:79], 10, v[72:73]
	v_lshl_add_u64 v[74:75], v[70:71], 0, v[74:75]
	v_or3_b32 v78, v78, v64, v69
	global_load_dwordx4 v[70:73], v[74:75], off
	v_lshlrev_b64 v[78:79], 2, v[78:79]
	v_lshl_add_u64 v[102:103], s[22:23], 0, v[78:79]
	v_lshl_add_u64 v[98:99], s[24:25], 0, v[78:79]
	global_load_dwordx4 v[78:81], v[98:99], off
	global_load_dwordx4 v[82:85], v[102:103], off
	global_load_dwordx4 v[86:89], v[74:75], off offset:16
	global_load_dwordx4 v[90:93], v[74:75], off offset:32
	global_load_dwordx4 v[94:97], v[74:75], off offset:48
	s_nop 0
	global_load_dwordx4 v[98:101], v[98:99], off offset:16
	s_nop 0
	global_load_dwordx4 v[102:105], v[102:103], off offset:16
	v_and_b32_e32 v64, 8, v68
	v_cmp_eq_u32_e32 vcc, 0, v64
	s_waitcnt vmcnt(0)
	v_mov_b32_e32 v106, v78
	v_mov_b32_e32 v107, v83
	s_waitcnt lgkmcnt(0)
	v_mov_b32_e32 v69, v72
	v_mov_b32_e32 v75, v72
	v_mov_b32_e32 v72, v71
	v_mov_b32_e32 v68, v71
	v_mov_b32_e32 v74, v70
	v_mov_b32_e32 v71, v73
	v_mov_b32_e32 v109, v88
	v_mov_b32_e32 v88, v87
	v_mov_b32_e32 v87, v92
	v_mov_b32_e32 v92, v91
	v_mov_b32_e32 v91, v96
	v_mov_b32_e32 v96, v95
	v_pk_mul_f32 v[72:73], v[78:79], v[72:73]
	v_mov_b32_e32 v108, v86
	v_mov_b32_e32 v86, v90
	v_mov_b32_e32 v90, v94
	v_pk_mul_f32 v[70:71], v[106:107], v[70:71]
	v_pk_mul_f32 v[94:95], v[80:81], v[88:89]
	v_pk_mul_f32 v[88:89], v[84:85], v[88:89]
	v_pk_mul_f32 v[106:107], v[98:99], v[92:93]
	v_pk_mul_f32 v[92:93], v[102:103], v[92:93]
	v_pk_mul_f32 v[110:111], v[100:101], v[96:97]
	v_pk_mul_f32 v[96:97], v[104:105], v[96:97]
	v_pk_fma_f32 v[72:73], v[82:83], v[74:75], v[72:73] neg_lo:[0,0,1] neg_hi:[0,0,1]
	v_mov_b32_e32 v83, v79
	v_pk_fma_f32 v[74:75], v[84:85], v[108:109], v[94:95] neg_lo:[0,0,1] neg_hi:[0,0,1]
	v_pk_fma_f32 v[78:79], v[80:81], v[108:109], v[88:89]
	v_pk_fma_f32 v[80:81], v[102:103], v[86:87], v[106:107] neg_lo:[0,0,1] neg_hi:[0,0,1]
	v_pk_fma_f32 v[84:85], v[98:99], v[86:87], v[92:93]
	v_pk_fma_f32 v[86:87], v[104:105], v[90:91], v[110:111] neg_lo:[0,0,1] neg_hi:[0,0,1]
	v_pk_fma_f32 v[88:89], v[100:101], v[90:91], v[96:97]
	v_pk_fma_f32 v[68:69], v[82:83], v[68:69], v[70:71]
	v_cndmask_b32_e64 v78, -v78, v74, vcc
	v_cndmask_b32_e64 v67, -v68, v72, vcc
	v_cndmask_b32_e64 v77, -v69, v73, vcc
	v_cndmask_b32_e64 v79, -v79, v75, vcc
	v_cndmask_b32_e64 v80, -v84, v80, vcc
	v_cndmask_b32_e64 v81, -v85, v81, vcc
	v_cndmask_b32_e64 v82, -v88, v86, vcc
	v_cndmask_b32_e64 v83, -v89, v87, vcc
.Lmy_exp_152:
	s_andn2_saveexec_b64 s[56:57], s[36:37]
	s_cbranch_execz .Lmy_exp_149
	v_ashrrev_i32_e32 v75, 1, v68
	v_lshlrev_b32_e32 v68, 5, v63
	v_lshl_or_b32 v70, v61, 1, v68
	v_ashrrev_i32_e32 v71, 31, v70
	v_lshlrev_b64 v[68:69], 15, v[70:71]
	v_or_b32_e32 v70, 1, v70
	v_ashrrev_i32_e32 v71, 31, v70
	v_lshlrev_b64 v[70:71], 15, v[70:71]
	v_and_b32_e32 v67, 8, v66
	v_lshl_add_u64 v[68:69], s[42:43], 0, v[68:69]
	v_lshl_add_u64 v[70:71], s[42:43], 0, v[70:71]
	v_lshl_add_u64 v[68:69], v[68:69], 0, v[64:65]
	v_lshlrev_b32_e32 v72, 2, v67
	v_mov_b32_e32 v73, v65
	v_lshl_add_u64 v[70:71], v[70:71], 0, v[64:65]
	v_sub_u32_e32 v64, v75, v74
	v_lshl_add_u64 v[68:69], v[68:69], 0, v[72:73]
	v_lshl_add_u64 v[72:73], v[70:71], 0, v[72:73]
	v_lshlrev_b64 v[70:71], 10, v[64:65]
	v_cmp_ge_i32_e64 s[36:37], v75, v74
	v_cmp_le_i32_e32 vcc, v75, v74
	v_lshl_add_u64 v[70:71], v[72:73], 0, v[70:71]
	s_and_saveexec_b64 s[58:59], s[36:37]
	s_xor_b64 s[58:59], exec, s[58:59]
	s_cbranch_execz .Lmy_exp_159
	s_and_saveexec_b64 s[18:19], vcc
	s_xor_b64 s[18:19], exec, s[18:19]
	s_cbranch_execz .Lmy_exp_156
	global_load_dword v64, v[68:69], off
	global_load_dword v67, v[72:73], off
	s_waitcnt vmcnt(0) lgkmcnt(0)
	v_add_f32_e32 v67, v64, v67
.Lmy_exp_156:
	s_andn2_saveexec_b64 s[18:19], s[18:19]
	s_cbranch_execz .Lmy_exp_158
	global_load_dword v67, v[70:71], off

; __global__ void __launch_bounds__(512, 2) fwd_kernel(KArgs a) {
;     ...
;                         const float* kf = KT + ((size_t)((ll * 16 + g) * 2 + 0) * 32) * 256 + i * 16 + j0; const float* kb = KT + ((size_t)((ll * 16 + g) * 2 + 1) * 32) * 256 + i * 16 + j0;
; #pragma unroll
;                         for (int j = 0; j < 8; ++j) v[j] = sp < s ? kf[(size_t)(s - sp) * 256 + j] : (sp > s ? kb[(size_t)(sp - s) * 256 + j] : kf[j] + kb[j]);
.Lmy_exp_159:
	s_or_saveexec_b64 s[58:59], s[58:59]
	v_sub_u32_e32 v64, v74, v75
	v_lshlrev_b64 v[74:75], 10, v[64:65]
	v_lshl_add_u64 v[74:75], v[68:69], 0, v[74:75]
	s_xor_b64 exec, exec, s[58:59]
	s_cbranch_execz .Lmy_exp_161
	s_waitcnt vmcnt(0) lgkmcnt(0)
	global_load_dword v67, v[74:75], off
.Lmy_exp_161:
	s_or_b64 exec, exec, s[58:59]
	s_and_saveexec_b64 s[58:59], s[36:37]
	s_xor_b64 s[58:59], exec, s[58:59]
	s_cbranch_execz .Lmy_exp_167
	s_and_saveexec_b64 s[18:19], vcc
	s_xor_b64 s[18:19], exec, s[18:19]
	s_cbranch_execz .Lmy_exp_164
	global_load_dword v64, v[68:69], off offset:4
	global_load_dword v77, v[72:73], off offset:4
	s_waitcnt vmcnt(0) lgkmcnt(0)
	v_add_f32_e32 v77, v64, v77
.Lmy_exp_164:
	s_andn2_saveexec_b64 s[18:19], s[18:19]
	s_cbranch_execz .Lmy_exp_166
	global_load_dword v77, v[70:71], off offset:4

; __global__ void __launch_bounds__(512, 2) fwd_kernel(KArgs a) {
;     ...
;                         const float* kf = KT + ((size_t)((ll * 16 + g) * 2 + 0) * 32) * 256 + i * 16 + j0; const float* kb = KT + ((size_t)((ll * 16 + g) * 2 + 1) * 32) * 256 + i * 16 + j0;
; #pragma unroll
;                         for (int j = 0; j < 8; ++j) v[j] = sp < s ? kf[(size_t)(s - sp) * 256 + j] : (sp > s ? kb[(size_t)(sp - s) * 256 + j] : kf[j] + kb[j]);
.Lmy_exp_168:
	s_waitcnt vmcnt(0) lgkmcnt(0)
	global_load_dword v77, v[74:75], off offset:4
.Lmy_exp_169:
	s_or_b64 exec, exec, s[58:59]
	s_and_saveexec_b64 s[58:59], s[36:37]
	s_xor_b64 s[58:59], exec, s[58:59]
	s_cbranch_execz .Lmy_exp_175
	s_and_saveexec_b64 s[18:19], vcc
	s_xor_b64 s[18:19], exec, s[18:19]
	s_cbranch_execz .Lmy_exp_172
	global_load_dword v64, v[68:69], off offset:8
	global_load_dword v78, v[72:73], off offset:8
	s_waitcnt vmcnt(0) lgkmcnt(0)
	v_add_f32_e32 v78, v64, v78
.Lmy_exp_172:
	s_andn2_saveexec_b64 s[18:19], s[18:19]
	s_cbranch_execz .Lmy_exp_174
	global_load_dword v78, v[70:71], off offset:8

; __global__ void __launch_bounds__(512, 2) fwd_kernel(KArgs a) {
;     ...
;                         const float* kf = KT + ((size_t)((ll * 16 + g) * 2 + 0) * 32) * 256 + i * 16 + j0; const float* kb = KT + ((size_t)((ll * 16 + g) * 2 + 1) * 32) * 256 + i * 16 + j0;
; #pragma unroll
;                         for (int j = 0; j < 8; ++j) v[j] = sp < s ? kf[(size_t)(s - sp) * 256 + j] : (sp > s ? kb[(size_t)(sp - s) * 256 + j] : kf[j] + kb[j]);
.Lmy_exp_176:
	s_waitcnt vmcnt(0) lgkmcnt(0)
	global_load_dword v78, v[74:75], off offset:8
.Lmy_exp_177:
	s_or_b64 exec, exec, s[58:59]
	s_and_saveexec_b64 s[58:59], s[36:37]
	s_xor_b64 s[58:59], exec, s[58:59]
	s_cbranch_execz .Lmy_exp_183
	s_and_saveexec_b64 s[18:19], vcc
	s_xor_b64 s[18:19], exec, s[18:19]
	s_cbranch_execz .Lmy_exp_180
	global_load_dword v64, v[68:69], off offset:12
	global_load_dword v79, v[72:73], off offset:12
	s_waitcnt vmcnt(0) lgkmcnt(0)
	v_add_f32_e32 v79, v64, v79
.Lmy_exp_180:
	s_andn2_saveexec_b64 s[18:19], s[18:19]
	s_cbranch_execz .Lmy_exp_182
	global_load_dword v79, v[70:71], off offset:12

; __global__ void __launch_bounds__(512, 2) fwd_kernel(KArgs a) {
;     ...
;                         const float* kf = KT + ((size_t)((ll * 16 + g) * 2 + 0) * 32) * 256 + i * 16 + j0; const float* kb = KT + ((size_t)((ll * 16 + g) * 2 + 1) * 32) * 256 + i * 16 + j0;
; #pragma unroll
;                         for (int j = 0; j < 8; ++j) v[j] = sp < s ? kf[(size_t)(s - sp) * 256 + j] : (sp > s ? kb[(size_t)(sp - s) * 256 + j] : kf[j] + kb[j]);
.Lmy_exp_184:
	s_waitcnt vmcnt(0) lgkmcnt(0)
	global_load_dword v79, v[74:75], off offset:12
.Lmy_exp_185:
	s_or_b64 exec, exec, s[58:59]
	s_and_saveexec_b64 s[58:59], s[36:37]
	s_xor_b64 s[58:59], exec, s[58:59]
	s_cbranch_execz .Lmy_exp_191
	s_and_saveexec_b64 s[18:19], vcc
	s_xor_b64 s[18:19], exec, s[18:19]
	s_cbranch_execz .Lmy_exp_188
	global_load_dword v64, v[68:69], off offset:16
	global_load_dword v80, v[72:73], off offset:16
	s_waitcnt vmcnt(0) lgkmcnt(0)
	v_add_f32_e32 v80, v64, v80
.Lmy_exp_188:
	s_andn2_saveexec_b64 s[18:19], s[18:19]
	s_cbranch_execz .Lmy_exp_190
	global_load_dword v80, v[70:71], off offset:16

; __global__ void __launch_bounds__(512, 2) fwd_kernel(KArgs a) {
;     ...
;                         const float* kf = KT + ((size_t)((ll * 16 + g) * 2 + 0) * 32) * 256 + i * 16 + j0; const float* kb = KT + ((size_t)((ll * 16 + g) * 2 + 1) * 32) * 256 + i * 16 + j0;
; #pragma unroll
;                         for (int j = 0; j < 8; ++j) v[j] = sp < s ? kf[(size_t)(s - sp) * 256 + j] : (sp > s ? kb[(size_t)(sp - s) * 256 + j] : kf[j] + kb[j]);
.Lmy_exp_192:
	s_waitcnt vmcnt(0) lgkmcnt(0)
	global_load_dword v80, v[74:75], off offset:16
.Lmy_exp_193:
	s_or_b64 exec, exec, s[58:59]
	s_and_saveexec_b64 s[58:59], s[36:37]
	s_xor_b64 s[58:59], exec, s[58:59]
	s_cbranch_execz .Lmy_exp_199
	s_and_saveexec_b64 s[18:19], vcc
	s_xor_b64 s[18:19], exec, s[18:19]
	s_cbranch_execz .Lmy_exp_196
	global_load_dword v64, v[68:69], off offset:20
	global_load_dword v81, v[72:73], off offset:20
	s_waitcnt vmcnt(0) lgkmcnt(0)
	v_add_f32_e32 v81, v64, v81
.Lmy_exp_196:
	s_andn2_saveexec_b64 s[18:19], s[18:19]
	s_cbranch_execz .Lmy_exp_198
	global_load_dword v81, v[70:71], off offset:20

; __global__ void __launch_bounds__(512, 2) fwd_kernel(KArgs a) {
;     ...
;                         const float* kf = KT + ((size_t)((ll * 16 + g) * 2 + 0) * 32) * 256 + i * 16 + j0; const float* kb = KT + ((size_t)((ll * 16 + g) * 2 + 1) * 32) * 256 + i * 16 + j0;
; #pragma unroll
;                         for (int j = 0; j < 8; ++j) v[j] = sp < s ? kf[(size_t)(s - sp) * 256 + j] : (sp > s ? kb[(size_t)(sp - s) * 256 + j] : kf[j] + kb[j]);
.Lmy_exp_200:
	s_waitcnt vmcnt(0) lgkmcnt(0)
	global_load_dword v81, v[74:75], off offset:20
.Lmy_exp_201:
	s_or_b64 exec, exec, s[58:59]
	s_and_saveexec_b64 s[58:59], s[36:37]
	s_xor_b64 s[58:59], exec, s[58:59]
	s_cbranch_execz .Lmy_exp_207
	s_and_saveexec_b64 s[18:19], vcc
	s_xor_b64 s[18:19], exec, s[18:19]
	s_cbranch_execz .Lmy_exp_204
	global_load_dword v64, v[68:69], off offset:24
	global_load_dword v82, v[72:73], off offset:24
	s_waitcnt vmcnt(0) lgkmcnt(0)
	v_add_f32_e32 v82, v64, v82
.Lmy_exp_204:
	s_andn2_saveexec_b64 s[18:19], s[18:19]
	s_cbranch_execz .Lmy_exp_206
	global_load_dword v82, v[70:71], off offset:24

; __global__ void __launch_bounds__(512, 2) fwd_kernel(KArgs a) {
;     ...
;                         const float* kf = KT + ((size_t)((ll * 16 + g) * 2 + 0) * 32) * 256 + i * 16 + j0; const float* kb = KT + ((size_t)((ll * 16 + g) * 2 + 1) * 32) * 256 + i * 16 + j0;
; #pragma unroll
;                         for (int j = 0; j < 8; ++j) v[j] = sp < s ? kf[(size_t)(s - sp) * 256 + j] : (sp > s ? kb[(size_t)(sp - s) * 256 + j] : kf[j] + kb[j]);
.Lmy_exp_208:
	s_waitcnt vmcnt(0) lgkmcnt(0)
	global_load_dword v82, v[74:75], off offset:24
.Lmy_exp_209:
	s_or_b64 exec, exec, s[58:59]
	s_and_saveexec_b64 s[58:59], s[36:37]
	s_xor_b64 s[36:37], exec, s[58:59]
	s_cbranch_execz .Lmy_exp_215
	s_and_saveexec_b64 s[58:59], vcc
	s_xor_b64 s[58:59], exec, s[58:59]
	s_cbranch_execz .Lmy_exp_212
	global_load_dword v64, v[68:69], off offset:28
	s_nop 0
	global_load_dword v68, v[72:73], off offset:28
	s_waitcnt vmcnt(0) lgkmcnt(0)
	v_add_f32_e32 v83, v64, v68
.Lmy_exp_212:
	s_andn2_saveexec_b64 s[58:59], s[58:59]
	s_cbranch_execz .Lmy_exp_214
	global_load_dword v83, v[70:71], off offset:28

; __device__ __forceinline__ unsigned cvt_pk_bf16(float lo, float hi) { unsigned r; asm volatile("v_cvt_pk_bf16_f32 %0, %1, %2" : "=v"(r) : "v"(lo), "v"(hi)); return r; }
; __global__ void __launch_bounds__(512, 2) fwd_kernel(KArgs a) {
;     ...
;                         for (int j = 0; j < 8; ++j) v[j] = sp < s ? kf[(size_t)(s - sp) * 256 + j] : (sp > s ? kb[(size_t)(sp - s) * 256 + j] : kf[j] + kb[j]);
;     ...
;                     u32x4 o; o.x = cvt_pk_bf16(v[0], v[1]); o.y = cvt_pk_bf16(v[2], v[3]); o.z = cvt_pk_bf16(v[4], v[5]); o.w = cvt_pk_bf16(v[6], v[7]);
;                     *(u32x4*)(BM2 + ((size_t)(ll * 16 + g) * 512 + n) * 768 + k0) = o;
.Lmy_exp_216:
	s_waitcnt vmcnt(0) lgkmcnt(0)
	global_load_dword v83, v[74:75], off offset:28
	s_branch .Lmy_exp_148

; __device__ __forceinline__ int opaque_tid() { int t; asm volatile("v_mov_b32 %0, %1" : "=v"(t) : "v"((int)threadIdx.x)); return t; }
; #define UNPK8(VV_, XX_) float XX_[8] = {bflo((VV_).x), bfhi((VV_).x), bflo((VV_).y), bfhi((VV_).y), bflo((VV_).z), bfhi((VV_).z), bflo((VV_).w), bfhi((VV_).w)}
; __device__ __forceinline__ void qproj_block(LAS unsigned char* lds, int bt, int l, const float* qnorm, const float* qgain, const bf16_t* P, const bf16_t* WUQ, bf16_t* QB) {
;     const int tid = opaque_tid(), lane = tid & 63, wave = __builtin_amdgcn_readfirstlane(tid >> 6), fr = lane & 15, fq = lane >> 4;
;     constexpr int RST = 528, BUF = 96 * RST;
;     const int row = bt * 128 + wave * 16 + fr; const bool isc = row >= ML; const int tpos = row & 2047;
;     const float qsc = 0.14724444383f;
;     bf16x8 bfr[8]; float ss = 0.f; u32x4 raw[8];
; #pragma unroll
;     for (int ks = 0; ks < 8; ++ks) { raw[ks] = ld8(P + (size_t)row * INP + OFF_CQ + ks * 32 + fq * 8); UNPK8(raw[ks], x);
;         ss += (x[0] * x[0] + x[1] * x[1]) + (x[2] * x[2] + x[3] * x[3]) + (x[4] * x[4] + x[5] * x[5]) + (x[6] * x[6] + x[7] * x[7]); }
;     ss += __shfl_xor(ss, 16); ss += __shfl_xor(ss, 32);
;     const float rinv = rsqrtf(ss * (1.f / 256.f) + EPS);
.LBB0_416:
	v_mov_b32 v62, v194
	s_lshl_b32 s7, s5, 7
	v_readfirstlane_b32 s1, v62
	s_ashr_i32 s1, s1, 2
	s_and_b32 s6, s1, -16
	v_and_b32_e32 v73, 15, v62
	s_add_i32 s7, s6, s7
	v_bfe_u32 v72, v62, 4, 2
	v_or_b32_e32 v104, s7, v73
	v_mov_b64_e32 v[2:3], s[40:41]
	v_mad_i64_i32 v[2:3], s[18:19], v104, s84, v[2:3]
	v_lshlrev_b32_e32 v0, 4, v72
	v_lshl_add_u64 v[2:3], v[2:3], 0, v[0:1]
	s_mov_b32 s1, 0x8eb8000
	v_add_co_u32_e32 v4, vcc, s1, v2
	s_mov_b64 s[18:19], 0x8eb8540
	s_nop 0
	v_addc_co_u32_e32 v5, vcc, 0, v3, vcc
	global_load_dwordx4 v[6:9], v[4:5], off offset:1344
	v_lshl_add_u64 v[22:23], v[2:3], 0, s[18:19]
	global_load_dwordx4 v[14:17], v[22:23], off offset:64
	global_load_dwordx4 v[24:27], v[22:23], off offset:128
	global_load_dwordx4 v[18:21], v[22:23], off offset:192
	global_load_dwordx4 v[28:31], v[22:23], off offset:256
	global_load_dwordx4 v[32:35], v[22:23], off offset:320
	global_load_dwordx4 v[2:5], v[22:23], off offset:384
	global_load_dwordx4 v[38:41], v[22:23], off offset:448
	v_readlane_b32 s14, v254, 23
	v_lshlrev_b32_e32 v94, 5, v72
	v_readlane_b32 s15, v254, 24
	v_lshlrev_b32_e32 v106, 2, v72
	s_add_i32 s6, s4, s6
	s_mov_b32 s1, 0
	v_cmp_gt_u32_e64 s[36:37], 2, v72
	s_waitcnt vmcnt(0) lgkmcnt(0)
	v_lshlrev_b32_e32 v57, 16, v15
	v_lshlrev_b32_e32 v55, 16, v17
	v_lshlrev_b32_e32 v63, 16, v19
	v_and_b32_e32 v92, 0xffff0000, v19
	v_lshlrev_b32_e32 v66, 16, v7
	v_and_b32_e32 v67, 0xffff0000, v7
	v_lshlrev_b32_e32 v65, 16, v6
	v_and_b32_e32 v61, 0xffff0000, v6
	v_lshlrev_b32_e32 v58, 16, v9
	v_and_b32_e32 v59, 0xffff0000, v9
	v_and_b32_e32 v7, 0xffff0000, v15
	v_and_b32_e32 v6, 0xffff0000, v14
	v_and_b32_e32 v9, 0xffff0000, v17
	v_and_b32_e32 v17, 0xffff0000, v24
	v_and_b32_e32 v15, 0xffff0000, v25
	v_lshlrev_b32_e32 v19, 16, v21
	v_lshlrev_b32_e32 v64, 16, v8
	v_and_b32_e32 v60, 0xffff0000, v8
	v_lshlrev_b32_e32 v56, 16, v14
	v_lshlrev_b32_e32 v54, 16, v16
	v_and_b32_e32 v8, 0xffff0000, v16
	v_lshlrev_b32_e32 v16, 16, v24
	v_lshlrev_b32_e32 v14, 16, v25
	v_pk_mul_f32 v[44:45], v[6:7], v[6:7]
	v_mul_f32_e32 v48, v17, v17
	v_mul_f32_e32 v50, v15, v15
	v_mov_b32_e32 v49, v19
	v_and_b32_e32 v23, 0xffff0000, v18
	v_and_b32_e32 v22, 0xffff0000, v26
	v_pk_mov_b32 v[36:37], v[26:27], v[20:21] op_sel:[1,0]
	v_pk_mul_f32 v[46:47], v[8:9], v[8:9]
	v_mul_f32_e32 v76, v63, v63
	v_mul_f32_e32 v77, v92, v92
	v_pk_fma_f32 v[44:45], v[56:57], v[56:57], v[44:45]
	v_pk_fma_f32 v[70:71], v[16:17], v[16:17], v[48:49] op_sel_hi:[1,1,0]
	v_pk_fma_f32 v[50:51], v[14:15], v[14:15], v[50:51] op_sel_hi:[1,1,0]
	v_and_b32_e32 v93, 0xffff0000, v21
	v_lshlrev_b32_e32 v25, 16, v18
	v_lshlrev_b32_e32 v24, 16, v26
	v_lshlrev_b32_e32 v21, 16, v20
	v_lshlrev_b32_e32 v20, 16, v27
	v_and_b32_e32 v27, 0xffff0000, v37
	v_and_b32_e32 v26, 0xffff0000, v36
	v_pk_mul_f32 v[36:37], v[22:23], v[22:23]
	v_pk_fma_f32 v[46:47], v[54:55], v[54:55], v[46:47]
	v_pk_add_f32 v[44:45], v[44:45], v[44:45] op_sel:[0,1] op_sel_hi:[1,0]
	v_mov_b32_e32 v71, v76
	v_mov_b32_e32 v51, v77
	v_pk_fma_f32 v[36:37], v[24:25], v[24:25], v[36:37]
	v_pk_mul_f32 v[74:75], v[26:27], v[26:27]
	v_pk_add_f32 v[44:45], v[46:47], v[44:45]
	v_pk_add_f32 v[50:51], v[70:71], v[50:51]
	v_mul_f32_e32 v78, v93, v93
	v_pk_fma_f32 v[74:75], v[20:21], v[20:21], v[74:75]
	v_pk_add_f32 v[36:37], v[36:37], v[50:51]
	v_pk_add_f32 v[44:45], v[46:47], v[44:45] op_sel:[1,0] op_sel_hi:[0,1]
	v_pk_add_f32 v[36:37], v[74:75], v[36:37]
	v_mov_b32_e32 v45, v78
	global_load_dwordx4 v[74:77], v94, s[14:15] offset:16
	global_load_dwordx4 v[78:81], v94, s[14:15]
	v_mul_f32_e32 v18, v67, v67
	v_pk_mul_f32 v[42:43], v[60:61], v[60:61]
	v_pk_fma_f32 v[68:69], v[66:67], v[66:67], v[18:19] op_sel_hi:[1,1,0]
	v_pk_fma_f32 v[42:43], v[64:65], v[64:65], v[42:43]
	v_mul_f32_e32 v52, v59, v59
	v_pk_add_f32 v[68:69], v[42:43], v[68:69] op_sel:[1,0] op_sel_hi:[0,1]
	v_pk_fma_f32 v[52:53], v[58:59], v[58:59], v[52:53] op_sel_hi:[1,1,0]
	v_pk_add_f32 v[42:43], v[42:43], v[68:69]
	v_mov_b32_e32 v18, v52
	v_mov_b32_e32 v48, v42
	v_pk_add_f32 v[42:43], v[52:53], v[42:43]
	v_pk_mul_f32 v[46:47], v[18:19], v[48:49]
	v_and_b32_e32 v51, 0xffff0000, v29
	v_and_b32_e32 v50, 0xffff0000, v28
	v_mov_b32_e32 v43, v47
	v_lshlrev_b32_e32 v53, 16, v29
	v_lshlrev_b32_e32 v52, 16, v28
	v_pk_mul_f32 v[28:29], v[50:51], v[50:51]
	v_and_b32_e32 v47, 0xffff0000, v31
	v_and_b32_e32 v46, 0xffff0000, v30
	v_pk_fma_f32 v[28:29], v[52:53], v[52:53], v[28:29]
	v_lshlrev_b32_e32 v49, 16, v31
	v_lshlrev_b32_e32 v48, 16, v30
	v_pk_mul_f32 v[30:31], v[46:47], v[46:47]
	v_pk_add_f32 v[28:29], v[28:29], v[28:29] op_sel:[0,1] op_sel_hi:[1,0]
	v_pk_fma_f32 v[30:31], v[48:49], v[48:49], v[30:31]
	v_pk_add_f32 v[42:43], v[42:43], v[44:45]
	v_pk_add_f32 v[28:29], v[30:31], v[28:29]
	v_lshlrev_b32_e32 v45, 16, v33
	v_lshlrev_b32_e32 v44, 16, v32
	v_and_b32_e32 v33, 0xffff0000, v33
	v_and_b32_e32 v32, 0xffff0000, v32
	v_pk_add_f32 v[84:85], v[30:31], v[28:29] op_sel:[1,0] op_sel_hi:[0,1]
	v_pk_mul_f32 v[28:29], v[32:33], v[32:33]
	v_pk_add_f32 v[82:83], v[42:43], v[36:37]
	v_pk_fma_f32 v[28:29], v[44:45], v[44:45], v[28:29]
	v_lshlrev_b32_e32 v31, 16, v35
	v_pk_add_f32 v[36:37], v[28:29], v[28:29] op_sel:[0,1] op_sel_hi:[1,0]
	v_and_b32_e32 v29, 0xffff0000, v35
	v_and_b32_e32 v28, 0xffff0000, v34
	v_lshlrev_b32_e32 v30, 16, v34
	v_pk_mul_f32 v[34:35], v[28:29], v[28:29]
	v_and_b32_e32 v71, 0xffff0000, v2
	v_pk_fma_f32 v[86:87], v[30:31], v[30:31], v[34:35]
	v_lshlrev_b32_e32 v70, 16, v2
	v_pk_add_f32 v[88:89], v[86:87], v[36:37]
	v_lshlrev_b32_e32 v68, 16, v3
	v_and_b32_e32 v69, 0xffff0000, v3
	v_lshlrev_b32_e32 v95, 16, v39
	v_and_b32_e32 v96, 0xffff0000, v39
; __device__ __forceinline__ unsigned cvt_pk_bf16(float lo, float hi) { unsigned r; asm volatile("v_cvt_pk_bf16_f32 %0, %1, %2" : "=v"(r) : "v"(lo), "v"(hi)); return r; }
; #define UNPK8(VV_, XX_) float XX_[8] = {bflo((VV_).x), bfhi((VV_).x), bflo((VV_).y), bfhi((VV_).y), bflo((VV_).z), bfhi((VV_).z), bflo((VV_).w), bfhi((VV_).w)}
; __device__ __forceinline__ void qproj_block(LAS unsigned char* lds, int bt, int l, const float* qnorm, const float* qgain, const bf16_t* P, const bf16_t* WUQ, bf16_t* QB) {
;     ...
;     for (int ks = 0; ks < 8; ++ks) { raw[ks] = ld8(P + (size_t)row * INP + OFF_CQ + ks * 32 + fq * 8); UNPK8(raw[ks], x);
;         ss += (x[0] * x[0] + x[1] * x[1]) + (x[2] * x[2] + x[3] * x[3]) + (x[4] * x[4] + x[5] * x[5]) + (x[6] * x[6] + x[7] * x[7]); }
;     ss += __shfl_xor(ss, 16); ss += __shfl_xor(ss, 32);
;     const float rinv = rsqrtf(ss * (1.f / 256.f) + EPS);
; #pragma unroll
;     for (int ks = 0; ks < 8; ++ks) { const float* gp = qnorm + l * 256 + ks * 32 + fq * 8; const f32x4 g0 = *(const f32x4*)gp, g1 = *(const f32x4*)(gp + 4); UNPK8(raw[ks], x); u32x4 o;
;         o.x = cvt_pk_bf16(x[0] * rinv * g0[0], x[1] * rinv * g0[1]); o.y = cvt_pk_bf16(x[2] * rinv * g0[2], x[3] * rinv * g0[3]);
;         o.z = cvt_pk_bf16(x[4] * rinv * g1[0], x[5] * rinv * g1[1]); o.w = cvt_pk_bf16(x[6] * rinv * g1[2], x[7] * rinv * g1[3]);
;         bfr[ks] = asfrag(o); }
;     u32x4 st[6];
	v_lshlrev_b32_e32 v37, 16, v38
	v_lshlrev_b32_e32 v36, 16, v4
	v_and_b32_e32 v39, 0xffff0000, v38
	v_and_b32_e32 v38, 0xffff0000, v4
	v_pk_mov_b32 v[2:3], v[4:5], v[40:41] op_sel:[1,0]
	v_mul_f32_e32 v4, v71, v71
	v_lshlrev_b32_e32 v35, 16, v41
	v_and_b32_e32 v97, 0xffff0000, v41
	v_mul_f32_e32 v18, v95, v95
	v_lshlrev_b32_e32 v41, 16, v40
	v_lshlrev_b32_e32 v40, 16, v5
	v_pk_fma_f32 v[4:5], v[70:71], v[70:71], v[4:5] op_sel_hi:[1,1,0]
	v_mul_f32_e32 v34, v96, v96
	v_mov_b32_e32 v5, v18
	v_mul_f32_e32 v18, v69, v69
	v_pk_fma_f32 v[90:91], v[68:69], v[68:69], v[18:19] op_sel_hi:[1,1,0]
	v_and_b32_e32 v43, 0xffff0000, v3
	v_and_b32_e32 v42, 0xffff0000, v2
	v_pk_mul_f32 v[2:3], v[38:39], v[38:39]
	v_mov_b32_e32 v91, v34
	v_pk_fma_f32 v[2:3], v[36:37], v[36:37], v[2:3]
	v_pk_add_f32 v[4:5], v[4:5], v[90:91]
	v_mul_f32_e32 v98, v97, v97
	v_pk_add_f32 v[2:3], v[2:3], v[4:5]
	v_pk_mul_f32 v[4:5], v[42:43], v[42:43]
	s_nop 0
	v_pk_fma_f32 v[4:5], v[40:41], v[40:41], v[4:5]
	s_nop 0
	v_pk_add_f32 v[2:3], v[4:5], v[2:3]
	v_pk_add_f32 v[4:5], v[82:83], v[82:83] op_sel:[0,1] op_sel_hi:[1,0]
	v_mov_b32_e32 v82, v84
	v_mov_b32_e32 v34, v4
	v_mov_b32_e32 v83, v35
	v_pk_add_f32 v[4:5], v[4:5], v[84:85]
	v_pk_mul_f32 v[82:83], v[34:35], v[82:83]
	s_nop 0
	v_mov_b32_e32 v5, v83
	v_pk_add_f32 v[82:83], v[86:87], v[88:89] op_sel:[1,0] op_sel_hi:[0,1]
	v_mov_b32_e32 v83, v98
	v_pk_add_f32 v[4:5], v[4:5], v[82:83]
	s_nop 0
	v_pk_add_f32 v[2:3], v[4:5], v[2:3]
	v_and_b32_e32 v4, 64, v199
	v_add_f32_e32 v2, v2, v3
	v_xor_b32_e32 v3, 16, v199
	v_add_u32_e32 v4, 64, v4
	v_cmp_lt_i32_e32 vcc, v3, v4
	s_nop 1
	v_cndmask_b32_e32 v3, v199, v3, vcc
	v_lshlrev_b32_e32 v107, 2, v3
	ds_bpermute_b32 v3, v107, v2
	s_waitcnt lgkmcnt(0)
	v_add_f32_e32 v2, v2, v3
	v_xor_b32_e32 v3, 32, v199
	v_cmp_lt_i32_e32 vcc, v3, v4
	s_nop 1
	v_cndmask_b32_e32 v3, v199, v3, vcc
	v_lshlrev_b32_e32 v105, 2, v3
	ds_bpermute_b32 v3, v105, v2
	s_waitcnt lgkmcnt(0)
	v_add_f32_e32 v2, v2, v3
	v_fmamk_f32 v2, v2, 0x3b800000, v197
	v_mul_f32_e32 v3, 0x4b800000, v2
	v_cmp_gt_f32_e32 vcc, s47, v2
	s_nop 1
	v_cndmask_b32_e32 v2, v2, v3, vcc
	v_rsq_f32_e32 v2, v2
	s_nop 0
	v_mul_f32_e32 v3, 0x45800000, v2
	v_cndmask_b32_e32 v34, v2, v3, vcc
	v_mul_f32_e32 v2, v34, v65
	v_mul_f32_e32 v3, v34, v61
	s_waitcnt vmcnt(0)
	v_mul_f32_e32 v2, v78, v2
	v_mul_f32_e32 v3, v79, v3
	v_cvt_pk_bf16_f32 v2, v2, v3
	v_mul_f32_e32 v3, v34, v66
	v_mul_f32_e32 v4, v34, v67
	v_mul_f32_e32 v3, v80, v3
	v_mul_f32_e32 v4, v81, v4
	v_cvt_pk_bf16_f32 v3, v3, v4
	v_mul_f32_e32 v4, v34, v64
	v_mul_f32_e32 v5, v34, v60
	v_mul_f32_e32 v4, v74, v4
	v_mul_f32_e32 v5, v75, v5
	v_cvt_pk_bf16_f32 v4, v4, v5
	v_mul_f32_e32 v5, v34, v58
	v_mul_f32_e32 v5, v76, v5
	v_mul_f32_e32 v18, v34, v59
	v_mul_f32_e32 v18, v77, v18
	v_cvt_pk_bf16_f32 v5, v5, v18
	global_load_dwordx4 v[58:61], v94, s[14:15] offset:128
	global_load_dwordx4 v[64:67], v94, s[14:15] offset:144
	v_mul_f32_e32 v18, v34, v56
	v_mul_f32_e32 v6, v34, v6
	v_mul_f32_e32 v7, v34, v7
	v_mul_f32_e32 v8, v34, v8
	v_mul_f32_e32 v9, v34, v9
	v_mul_f32_e32 v16, v34, v16
	v_mul_f32_e32 v17, v34, v17
	v_mul_f32_e32 v15, v34, v15
	v_mul_f32_e32 v14, v34, v14
	v_mul_f32_e32 v22, v34, v22
	v_mul_f32_e32 v20, v34, v20
	v_mul_f32_e32 v21, v34, v21
	v_mul_f32_e32 v19, v34, v19
	v_mul_f32_e32 v51, v34, v51
	v_mul_f32_e32 v46, v34, v46
	v_mul_f32_e32 v49, v34, v49
	v_mul_f32_e32 v47, v34, v47
	v_mul_f32_e32 v48, v34, v48
	v_mul_f32_e32 v33, v34, v33
	v_mul_f32_e32 v30, v34, v30
	v_mul_f32_e32 v28, v34, v28
	v_mul_f32_e32 v31, v34, v31
	v_mul_f32_e32 v29, v34, v29
	v_mul_f32_e32 v36, v34, v36
	v_mul_f32_e32 v38, v34, v38
	v_mul_f32_e32 v40, v34, v40
	v_mul_f32_e32 v42, v34, v42
	v_add_u32_e32 v74, 0xa00, v62
	v_ashrrev_i32_e32 v75, 31, v74
	v_mul_f32_e32 v35, v34, v35
	v_lshlrev_b64 v[110:111], 4, v[74:75]
	v_cmp_lt_i32_e32 vcc, s49, v104
	s_waitcnt vmcnt(1)
	v_mul_f32_e32 v18, v58, v18
	v_mul_f32_e32 v6, v59, v6
	v_cvt_pk_bf16_f32 v6, v18, v6
	v_mul_f32_e32 v18, v34, v57
	v_mul_f32_e32 v18, v60, v18
	v_mul_f32_e32 v7, v61, v7
	v_cvt_pk_bf16_f32 v7, v18, v7
	v_mul_f32_e32 v18, v34, v54
	s_waitcnt vmcnt(0)
	v_mul_f32_e32 v18, v64, v18
	v_mul_f32_e32 v8, v65, v8
	v_cvt_pk_bf16_f32 v8, v18, v8
	v_mul_f32_e32 v18, v34, v55
	v_mul_f32_e32 v9, v67, v9
	v_mul_f32_e32 v18, v66, v18
	v_cvt_pk_bf16_f32 v9, v18, v9
	global_load_dwordx4 v[54:57], v94, s[14:15] offset:256
	global_load_dwordx4 v[58:61], v94, s[14:15] offset:272
	v_mul_f32_e32 v18, v34, v24
	v_mul_f32_e32 v24, v34, v26
	v_add_u32_e32 v64, 0x200, v62
	v_add_u32_e32 v66, 0x400, v62
	v_ashrrev_i32_e32 v65, 31, v64
	v_ashrrev_i32_e32 v67, 31, v66
	v_lshlrev_b64 v[78:79], 4, v[64:65]
	v_lshlrev_b64 v[80:81], 4, v[66:67]
	v_lshl_add_u64 v[86:87], s[44:45], 0, v[80:81]
	s_waitcnt vmcnt(1)
	v_mul_f32_e32 v16, v54, v16
	v_mul_f32_e32 v17, v55, v17
	v_mul_f32_e32 v15, v57, v15
	v_mul_f32_e32 v26, v56, v14
	s_waitcnt vmcnt(0)
	v_mul_f32_e32 v18, v58, v18
	v_mul_f32_e32 v22, v59, v22
	v_mul_f32_e32 v20, v60, v20
	v_mul_f32_e32 v24, v61, v24
	v_cvt_pk_bf16_f32 v14, v16, v17
	v_cvt_pk_bf16_f32 v15, v26, v15
	v_cvt_pk_bf16_f32 v16, v18, v22
	v_cvt_pk_bf16_f32 v17, v20, v24
	global_load_dwordx4 v[54:57], v94, s[14:15] offset:384
	global_load_dwordx4 v[58:61], v94, s[14:15] offset:400
	v_mul_f32_e32 v18, v34, v25
	v_mul_f32_e32 v20, v34, v23
	v_mul_f32_e32 v22, v34, v63
	v_mul_f32_e32 v23, v34, v92
	v_mul_f32_e32 v24, v34, v27
	v_mul_f32_e32 v25, v34, v93
	v_mul_f32_e32 v27, v34, v50
	v_mul_f32_e32 v50, v34, v53
	v_ashrrev_i32_e32 v63, 31, v62
	v_lshlrev_b64 v[76:77], 4, v[62:63]
	v_lshl_add_u64 v[92:93], s[44:45], 0, v[110:111]
	v_mul_u32_u24_e32 v63, 0x210, v73
	v_add3_u32 v122, 0, v63, v0
	v_and_b32_e32 v63, 4, v106
	v_cvt_f32_ubyte0_e32 v65, v63
	v_mul_f32_e32 v65, 0xbfd49a78, v65
	v_or_b32_e32 v67, 1, v63
	v_exp_f32_e32 v65, v65
	v_cvt_f32_ubyte0_e32 v67, v67
	v_mul_f32_e32 v67, 0xbfd49a78, v67
	v_exp_f32_e32 v67, v67
	s_waitcnt vmcnt(1)
; __device__ __forceinline__ unsigned cvt_pk_bf16(float lo, float hi) { unsigned r; asm volatile("v_cvt_pk_bf16_f32 %0, %1, %2" : "=v"(r) : "v"(lo), "v"(hi)); return r; }
; #define UNPK8(VV_, XX_) float XX_[8] = {bflo((VV_).x), bfhi((VV_).x), bflo((VV_).y), bfhi((VV_).y), bflo((VV_).z), bfhi((VV_).z), bflo((VV_).w), bfhi((VV_).w)}
; #define QW_LOAD(h_) do { const bf16_t* wsrc_ = WUQ + ((size_t)l * 384 + (h_) * 96) * 256; _Pragma("unroll") for (int j_ = 0; j_ < 6; ++j_) st[j_] = ld8(wsrc_ + (size_t)(tid + j_ * 512) * 8); } while (0)
; __device__ __forceinline__ f32x4 rope16(f32x4 v, int fq, float pos) {
;     ...
;     for (int q = 0; q < 4; ++q) { const int f = (fq * 4 + q) & 7; const float inv = __builtin_amdgcn_exp2f(-(float)f * 1.6609640474f); float sn, cs; __sincosf(pos * inv, &sn, &cs);
; __device__ __forceinline__ void qproj_block(LAS unsigned char* lds, int bt, int l, const float* qnorm, const float* qgain, const bf16_t* P, const bf16_t* WUQ, bf16_t* QB) {
;     ...
;     for (int ks = 0; ks < 8; ++ks) { const float* gp = qnorm + l * 256 + ks * 32 + fq * 8; const f32x4 g0 = *(const f32x4*)gp, g1 = *(const f32x4*)(gp + 4); UNPK8(raw[ks], x); u32x4 o;
;         o.x = cvt_pk_bf16(x[0] * rinv * g0[0], x[1] * rinv * g0[1]); o.y = cvt_pk_bf16(x[2] * rinv * g0[2], x[3] * rinv * g0[3]);
;         o.z = cvt_pk_bf16(x[4] * rinv * g1[0], x[5] * rinv * g1[1]); o.w = cvt_pk_bf16(x[6] * rinv * g1[2], x[7] * rinv * g1[3]);
;         bfr[ks] = asfrag(o); }
;     u32x4 st[6];
;     ...
;     __syncthreads();
;     QW_LOAD(0);
	v_mul_f32_e32 v18, v18, v54
	v_mul_f32_e32 v20, v20, v55
	v_mul_f32_e32 v22, v22, v56
	v_mul_f32_e32 v23, v23, v57
	s_waitcnt vmcnt(0)
	v_mul_f32_e32 v21, v21, v58
	v_mul_f32_e32 v24, v24, v59
	v_mul_f32_e32 v25, v25, v61
	v_mul_f32_e32 v26, v19, v60
	v_cvt_pk_bf16_f32 v18, v18, v20
	v_cvt_pk_bf16_f32 v19, v22, v23
	v_cvt_pk_bf16_f32 v20, v21, v24
	v_cvt_pk_bf16_f32 v21, v26, v25
	global_load_dwordx4 v[22:25], v94, s[14:15] offset:512
	global_load_dwordx4 v[54:57], v94, s[14:15] offset:528
	v_mul_f32_e32 v26, v34, v52
	s_waitcnt vmcnt(1)
	v_mul_f32_e32 v22, v26, v22
	v_mul_f32_e32 v23, v27, v23
	v_mul_f32_e32 v24, v50, v24
	v_mul_f32_e32 v25, v51, v25
	s_waitcnt vmcnt(0)
	v_mul_f32_e32 v27, v46, v55
	v_mul_f32_e32 v46, v49, v56
	v_mul_f32_e32 v47, v47, v57
	v_mul_f32_e32 v26, v48, v54
	v_cvt_pk_bf16_f32 v22, v22, v23
	v_cvt_pk_bf16_f32 v23, v24, v25
	v_cvt_pk_bf16_f32 v24, v26, v27
	v_cvt_pk_bf16_f32 v25, v46, v47
	global_load_dwordx4 v[46:49], v94, s[14:15] offset:640
	global_load_dwordx4 v[50:53], v94, s[14:15] offset:656
	v_mul_f32_e32 v26, v34, v44
	v_mul_f32_e32 v27, v34, v32
	v_mul_f32_e32 v32, v34, v45
	v_lshl_add_u64 v[54:55], s[44:45], 0, v[78:79]
	s_waitcnt vmcnt(1)
	v_mul_f32_e32 v26, v26, v46
	v_mul_f32_e32 v27, v27, v47
	v_mul_f32_e32 v32, v32, v48
	v_mul_f32_e32 v33, v33, v49
	s_waitcnt vmcnt(0)
	v_mul_f32_e32 v30, v30, v50
	v_mul_f32_e32 v28, v28, v51
	v_mul_f32_e32 v31, v31, v52
	v_mul_f32_e32 v29, v29, v53
	v_cvt_pk_bf16_f32 v26, v26, v27
	v_cvt_pk_bf16_f32 v27, v32, v33
	v_cvt_pk_bf16_f32 v28, v30, v28
	v_cvt_pk_bf16_f32 v29, v31, v29
	global_load_dwordx4 v[30:33], v94, s[14:15] offset:768
	global_load_dwordx4 v[44:47], v94, s[14:15] offset:784
	v_mul_f32_e32 v48, v34, v70
	v_mul_f32_e32 v49, v34, v71
	v_mul_f32_e32 v50, v34, v68
	v_mul_f32_e32 v51, v34, v69
	v_add_u32_e32 v68, 0x600, v62
	v_add_u32_e32 v70, 0x800, v62
	v_ashrrev_i32_e32 v69, 31, v68
	v_ashrrev_i32_e32 v71, 31, v70
	v_lshl_add_u64 v[52:53], s[44:45], 0, v[76:77]
	v_lshlrev_b64 v[82:83], 4, v[68:69]
	v_lshlrev_b64 v[84:85], 4, v[70:71]
	v_lshl_add_u64 v[88:89], s[44:45], 0, v[82:83]
	v_lshl_add_u64 v[90:91], s[44:45], 0, v[84:85]
	v_or_b32_e32 v69, 2, v63
	v_or_b32_e32 v63, 3, v63
	v_cvt_f32_ubyte0_e32 v69, v69
	v_cvt_f32_ubyte0_e32 v63, v63
	v_mul_f32_e32 v69, 0xbfd49a78, v69
	v_mul_f32_e32 v63, 0xbfd49a78, v63
	v_exp_f32_e32 v69, v69
	v_exp_f32_e32 v63, v63
	s_waitcnt vmcnt(1)
	v_mul_f32_e32 v30, v48, v30
	v_mul_f32_e32 v31, v49, v31
	v_mul_f32_e32 v32, v50, v32
	v_mul_f32_e32 v33, v51, v33
	s_waitcnt vmcnt(0)
	v_mul_f32_e32 v36, v36, v44
	v_mul_f32_e32 v38, v38, v45
	v_mul_f32_e32 v40, v40, v46
	v_mul_f32_e32 v42, v42, v47
	v_cvt_pk_bf16_f32 v30, v30, v31
	v_cvt_pk_bf16_f32 v31, v32, v33
	v_cvt_pk_bf16_f32 v32, v36, v38
	v_cvt_pk_bf16_f32 v33, v40, v42
	global_load_dwordx4 v[44:47], v94, s[14:15] offset:896
	global_load_dwordx4 v[48:51], v94, s[14:15] offset:912
	v_lshlrev_b32_e32 v36, 4, v62
	v_and_b32_e32 v36, 0x1f0, v36
	v_add_u32_e32 v123, 0, v36
	v_mul_f32_e32 v36, v34, v37
	v_mul_f32_e32 v37, v34, v39
	v_mul_f32_e32 v38, v34, v95
	v_mul_f32_e32 v39, v34, v96
	v_mul_f32_e32 v40, v34, v41
	v_mul_f32_e32 v41, v34, v43
	v_mul_f32_e32 v34, v34, v97
	v_readlane_b32 s14, v254, 25
	v_readlane_b32 s15, v254, 26
	v_ashrrev_i32_e32 v62, 5, v62
	s_waitcnt vmcnt(1)
	v_mul_f32_e32 v36, v36, v44
	v_mul_f32_e32 v37, v37, v45
	v_mul_f32_e32 v38, v38, v46
	v_mul_f32_e32 v39, v39, v47
	s_waitcnt vmcnt(0)
	v_mul_f32_e32 v40, v40, v48
	v_mul_f32_e32 v41, v41, v49
	v_mul_f32_e32 v42, v35, v50
	v_mul_f32_e32 v43, v34, v51
	v_cvt_pk_bf16_f32 v34, v36, v37
	v_cvt_pk_bf16_f32 v35, v38, v39
	v_cvt_pk_bf16_f32 v36, v40, v41
	v_cvt_pk_bf16_f32 v37, v42, v43
	s_barrier
	global_load_dwordx4 v[58:61], v[52:53], off
	s_nop 0
	global_load_dwordx4 v[54:57], v[54:55], off
	s_nop 0
	global_load_dwordx4 v[50:53], v[86:87], off
	global_load_dwordx4 v[46:49], v[88:89], off
	global_load_dwordx4 v[42:45], v[90:91], off
	global_load_dwordx4 v[38:41], v[92:93], off
	v_lshl_add_u64 v[88:89], s[14:15], 0, v[0:1]
	s_bfe_u32 s14, s7, 0x50006
	v_bitop3_b32 v0, s7, 63, v73 bitop3:0xc8
	s_movk_i32 s7, 0x210
	v_mul_lo_u32 v124, v62, s7
	v_ashrrev_i32_e32 v62, 5, v64
	v_mul_lo_u32 v125, v62, s7
	v_ashrrev_i32_e32 v62, 5, v66
	v_mul_lo_u32 v126, v62, s7
	v_ashrrev_i32_e32 v62, 5, v68
	v_mul_lo_u32 v127, v62, s7
	v_ashrrev_i32_e32 v62, 5, v70
	v_mul_lo_u32 v128, v62, s7
	v_ashrrev_i32_e32 v62, 5, v74
	v_mul_lo_u32 v129, v62, s7
	v_cvt_f32_ubyte0_e32 v62, s14
	v_mul_f32_e32 v64, v65, v62
	v_mul_f32_e32 v64, 0.15915494, v64
	v_cos_f32_e32 v96, v64
	v_sin_f32_e32 v100, v64
	v_mul_f32_e32 v64, v67, v62
	v_mul_f32_e32 v64, 0.15915494, v64
	v_cos_f32_e32 v97, v64
	v_sin_f32_e32 v101, v64
	v_mul_f32_e32 v64, v69, v62
	v_mul_f32_e32 v62, v63, v62
	v_cvt_f32_ubyte0_e32 v0, v0
	v_mul_f32_e32 v62, 0.15915494, v62
	v_cos_f32_e32 v99, v62
	v_sin_f32_e32 v103, v62
	v_mul_f32_e32 v62, v67, v0
	v_mul_f32_e32 v62, 0.15915494, v62
	v_mul_f32_e32 v71, v65, v0
	v_cos_f32_e32 v87, v62
	v_sin_f32_e32 v91, v62
	v_mul_f32_e32 v62, v69, v0
	v_mul_f32_e32 v0, v63, v0
	v_mul_f32_e32 v0, 0.15915494, v0
	v_mul_f32_e32 v71, 0.15915494, v71
	v_mul_f32_e32 v64, 0.15915494, v64
	v_mul_f32_e32 v62, 0.15915494, v62
	v_cos_f32_e32 v93, v0
	v_sin_f32_e32 v95, v0
	v_add_u32_e32 v0, s6, v73
	v_cos_f32_e32 v86, v71
	v_cos_f32_e32 v98, v64
	v_sin_f32_e32 v102, v64
	v_sin_f32_e32 v90, v71
	v_cos_f32_e32 v92, v62
	v_sin_f32_e32 v94, v62
	v_mad_i64_i32 v[108:109], s[6:7], v0, s50, 0
	v_readlane_b32 s6, v250, 14
	v_readlane_b32 s7, v250, 15
	v_lshl_or_b32 v108, v72, 3, v108
	s_nop 0
	v_lshl_add_u64 v[110:111], s[6:7], 0, v[110:111]
	v_lshl_add_u64 v[112:113], s[6:7], 0, v[84:85]
	v_lshl_add_u64 v[114:115], s[6:7], 0, v[82:83]
	v_lshl_add_u64 v[116:117], s[6:7], 0, v[80:81]
	v_lshl_add_u64 v[118:119], s[6:7], 0, v[78:79]
	v_lshl_add_u64 v[120:121], s[6:7], 0, v[76:77]
; #define LAS __attribute__((address_space(3)))
; #define MFMA16(a, b, c) __builtin_amdgcn_mfma_f32_16x16x32_bf16((a), (b), (c), 0, 0, 0)
; #define QW_LOAD(h_) do { const bf16_t* wsrc_ = WUQ + ((size_t)l * 384 + (h_) * 96) * 256; _Pragma("unroll") for (int j_ = 0; j_ < 6; ++j_) st[j_] = ld8(wsrc_ + (size_t)(tid + j_ * 512) * 8); } while (0)
; #define QW_STORE(buf_) do { _Pragma("unroll") for (int j_ = 0; j_ < 6; ++j_) { const int p_ = tid + j_ * 512; *(LAS u32x4*)(lds + (buf_) * BUF + (p_ >> 5) * RST + (p_ & 31) * 16) = st[j_]; } } while (0)
; __device__ __forceinline__ void qproj_block(LAS unsigned char* lds, int bt, int l, const float* qnorm, const float* qgain, const bf16_t* P, const bf16_t* WUQ, bf16_t* QB) {
;     ...
;     for (int h = 0; h < 4; ++h) {
;         QW_STORE(h & 1);
;         __syncthreads();
;         if (h < 3) QW_LOAD(h + 1);
;         const LAS unsigned char* wb = lds + (h & 1) * BUF + fr * RST + fq * 16;
;         f32x4 acc[6];
; #pragma unroll
;         for (int cb = 0; cb < 6; ++cb) { acc[cb] = (f32x4){0.f, 0.f, 0.f, 0.f};
; #pragma unroll
;             for (int ks = 0; ks < 8; ++ks) acc[cb] = MFMA16(*(const LAS bf16x8*)(wb + cb * 16 * RST + ks * 64), bfr[ks], acc[cb]); }
.LBB0_417:
	s_bitcmp1_b32 s1, 0
	s_cselect_b32 s6, 0xc600, 0
	v_add_u32_e32 v0, s6, v123
	v_add_u32_e32 v62, v0, v124
	s_waitcnt vmcnt(0) lgkmcnt(0)
	ds_write_b128 v62, v[58:61]
	v_add_u32_e32 v58, v0, v125
	ds_write_b128 v58, v[54:57]
	v_add_u32_e32 v54, v0, v126
	ds_write_b128 v54, v[50:53]
	v_add_u32_e32 v50, v0, v127
	ds_write_b128 v50, v[46:49]
	v_add_u32_e32 v46, v0, v128
	v_add_u32_e32 v0, v0, v129
	ds_write_b128 v46, v[42:45]
	ds_write_b128 v0, v[38:41]
	v_add_u32_e32 v0, s6, v122
	s_waitcnt lgkmcnt(0)
	s_barrier
	ds_read_b128 v[62:65], v0
	ds_read_b128 v[66:69], v0 offset:64
	s_waitcnt lgkmcnt(1)
	v_mfma_f32_16x16x32_bf16 v[62:65], v[62:65], v[2:5], 0
	ds_read_b128 v[70:73], v0 offset:16960
	v_lshl_add_u64 v[38:39], s[40:41], 0, v[120:121]
	ds_read_b128 v[74:77], v0 offset:25408
	s_waitcnt lgkmcnt(2)
	v_mfma_f32_16x16x32_bf16 v[62:65], v[66:69], v[6:9], v[62:65]
	ds_read_b128 v[66:69], v0 offset:128
	global_load_dwordx4 v[58:61], v[38:39], off
	v_lshl_add_u64 v[38:39], s[40:41], 0, v[118:119]
	s_waitcnt lgkmcnt(0)
	v_mfma_f32_16x16x32_bf16 v[62:65], v[66:69], v[14:17], v[62:65]
	ds_read_b128 v[66:69], v0 offset:192
	global_load_dwordx4 v[54:57], v[38:39], off
	v_lshl_add_u64 v[38:39], s[40:41], 0, v[116:117]
	s_waitcnt lgkmcnt(0)
	v_mfma_f32_16x16x32_bf16 v[62:65], v[66:69], v[18:21], v[62:65]
	ds_read_b128 v[66:69], v0 offset:256
	global_load_dwordx4 v[50:53], v[38:39], off
	v_lshl_add_u64 v[38:39], s[40:41], 0, v[114:115]
	s_waitcnt lgkmcnt(0)
	v_mfma_f32_16x16x32_bf16 v[62:65], v[66:69], v[22:25], v[62:65]
	ds_read_b128 v[66:69], v0 offset:320
	global_load_dwordx4 v[46:49], v[38:39], off
	v_lshl_add_u64 v[38:39], s[40:41], 0, v[112:113]
	s_waitcnt lgkmcnt(0)
	v_mfma_f32_16x16x32_bf16 v[62:65], v[66:69], v[26:29], v[62:65]
	ds_read_b128 v[66:69], v0 offset:384
	global_load_dwordx4 v[42:45], v[38:39], off
	v_lshl_add_u64 v[38:39], s[40:41], 0, v[110:111]
	s_waitcnt lgkmcnt(0)
	v_mfma_f32_16x16x32_bf16 v[62:65], v[66:69], v[30:33], v[62:65]
	ds_read_b128 v[66:69], v0 offset:448
	s_mov_b32 s6, 0x6ab8000
	global_load_dwordx4 v[38:41], v[38:39], off
	s_waitcnt lgkmcnt(0)
	v_mfma_f32_16x16x32_bf16 v[82:85], v[66:69], v[34:37], v[62:65]
	s_nop 2
	ds_read_b128 v[62:65], v0 offset:8448
	ds_read_b128 v[66:69], v0 offset:8512
	s_add_i32 s1, s1, 1
	s_waitcnt lgkmcnt(0)
	v_mfma_f32_16x16x32_bf16 v[62:65], v[62:65], v[2:5], 0
	v_lshl_add_u64 v[110:111], v[110:111], 0, s[10:11]
	v_lshl_add_u64 v[112:113], v[112:113], 0, s[10:11]
	v_lshl_add_u64 v[114:115], v[114:115], 0, s[10:11]
	v_mfma_f32_16x16x32_bf16 v[62:65], v[66:69], v[6:9], v[62:65]
	ds_read_b128 v[66:69], v0 offset:8576
	v_lshl_add_u64 v[116:117], v[116:117], 0, s[10:11]
	v_lshl_add_u64 v[118:119], v[118:119], 0, s[10:11]
	s_waitcnt lgkmcnt(0)
	v_mfma_f32_16x16x32_bf16 v[62:65], v[66:69], v[14:17], v[62:65]
	ds_read_b128 v[66:69], v0 offset:8640
	v_lshl_add_u64 v[120:121], v[120:121], 0, s[10:11]
	s_cmp_lg_u32 s1, 3
	s_waitcnt lgkmcnt(0)
	v_mfma_f32_16x16x32_bf16 v[62:65], v[66:69], v[18:21], v[62:65]
	ds_read_b128 v[66:69], v0 offset:8704
	ds_read_b128 v[78:81], v0 offset:33856
	ds_read_b128 v[130:133], v0 offset:42304
	s_waitcnt lgkmcnt(0)
	v_mfma_f32_16x16x32_bf16 v[62:65], v[66:69], v[22:25], v[62:65]
	ds_read_b128 v[66:69], v0 offset:8768
	s_waitcnt lgkmcnt(0)
	v_mfma_f32_16x16x32_bf16 v[62:65], v[66:69], v[26:29], v[62:65]
	ds_read_b128 v[66:69], v0 offset:8832
	s_waitcnt lgkmcnt(0)
	v_mfma_f32_16x16x32_bf16 v[62:65], v[66:69], v[30:33], v[62:65]
	ds_read_b128 v[66:69], v0 offset:8896
	s_waitcnt lgkmcnt(0)
	v_mfma_f32_16x16x32_bf16 v[62:65], v[66:69], v[34:37], v[62:65]
	ds_read_b128 v[66:69], v0 offset:16896
	s_waitcnt lgkmcnt(0)
	v_mfma_f32_16x16x32_bf16 v[66:69], v[66:69], v[2:5], 0
	v_mfma_f32_16x16x32_bf16 v[66:69], v[70:73], v[6:9], v[66:69]
	ds_read_b128 v[70:73], v0 offset:17024
	s_waitcnt lgkmcnt(0)
	v_mfma_f32_16x16x32_bf16 v[66:69], v[70:73], v[14:17], v[66:69]
	ds_read_b128 v[70:73], v0 offset:17088
	s_waitcnt lgkmcnt(0)
	v_mfma_f32_16x16x32_bf16 v[66:69], v[70:73], v[18:21], v[66:69]
	ds_read_b128 v[70:73], v0 offset:17152
	s_waitcnt lgkmcnt(0)
	v_mfma_f32_16x16x32_bf16 v[66:69], v[70:73], v[22:25], v[66:69]
	ds_read_b128 v[70:73], v0 offset:17216
	s_waitcnt lgkmcnt(0)
	v_mfma_f32_16x16x32_bf16 v[66:69], v[70:73], v[26:29], v[66:69]
	ds_read_b128 v[70:73], v0 offset:17280
	s_waitcnt lgkmcnt(0)
	v_mfma_f32_16x16x32_bf16 v[66:69], v[70:73], v[30:33], v[66:69]
	ds_read_b128 v[70:73], v0 offset:17344
	s_waitcnt lgkmcnt(0)
	v_mfma_f32_16x16x32_bf16 v[66:69], v[70:73], v[34:37], v[66:69]
	ds_read_b128 v[70:73], v0 offset:25344
	s_nop 6
	v_mul_f32_e32 v134, v67, v67
	s_waitcnt lgkmcnt(0)
	v_mfma_f32_16x16x32_bf16 v[70:73], v[70:73], v[2:5], 0
	v_mul_f32_e32 v135, v68, v68
	v_mul_f32_e32 v136, v69, v69
	v_mfma_f32_16x16x32_bf16 v[70:73], v[74:77], v[6:9], v[70:73]
	ds_read_b128 v[74:77], v0 offset:25472
	s_waitcnt lgkmcnt(0)
	v_mfma_f32_16x16x32_bf16 v[70:73], v[74:77], v[14:17], v[70:73]
	ds_read_b128 v[74:77], v0 offset:25536
	s_waitcnt lgkmcnt(0)
	v_mfma_f32_16x16x32_bf16 v[70:73], v[74:77], v[18:21], v[70:73]
	ds_read_b128 v[74:77], v0 offset:25600
	s_waitcnt lgkmcnt(0)
	v_mfma_f32_16x16x32_bf16 v[70:73], v[74:77], v[22:25], v[70:73]
	ds_read_b128 v[74:77], v0 offset:25664
	s_waitcnt lgkmcnt(0)
	v_mfma_f32_16x16x32_bf16 v[70:73], v[74:77], v[26:29], v[70:73]
	ds_read_b128 v[74:77], v0 offset:25728
	s_waitcnt lgkmcnt(0)
	v_mfma_f32_16x16x32_bf16 v[70:73], v[74:77], v[30:33], v[70:73]
	ds_read_b128 v[74:77], v0 offset:25792
	s_waitcnt lgkmcnt(0)
	v_mfma_f32_16x16x32_bf16 v[70:73], v[74:77], v[34:37], v[70:73]
	ds_read_b128 v[74:77], v0 offset:33792
	s_waitcnt lgkmcnt(0)
; __device__ __forceinline__ unsigned cvt_pk_bf16(float lo, float hi) { unsigned r; asm volatile("v_cvt_pk_bf16_f32 %0, %1, %2" : "=v"(r) : "v"(lo), "v"(hi)); return r; }
; __device__ __forceinline__ void qproj_block(LAS unsigned char* lds, int bt, int l, const float* qnorm, const float* qgain, const bf16_t* P, const bf16_t* WUQ, bf16_t* QB) {
;     ...
;         float s2 = 0.f;
; #pragma unroll
;         for (int cb = 0; cb < 6; ++cb) s2 += (acc[cb][0] * acc[cb][0] + acc[cb][1] * acc[cb][1]) + (acc[cb][2] * acc[cb][2] + acc[cb][3] * acc[cb][3]);
;         s2 += __shfl_xor(s2, 16); s2 += __shfl_xor(s2, 32);
;         const float rh = rsqrtf(s2 * (1.f / 96.f) + EPS);
; #pragma unroll
;         for (int cb = 0; cb < 6; ++cb) { const f32x4 qg = *(const f32x4*)(qgain + l * 96 + cb * 16 + fq * 4); f32x4 v = acc[cb] * rh * qg;
;             if (cb >= 4) { const f32x4 rv = rope16(v, fq, (float)(cb == 4 ? (tpos >> 6) : (tpos & 63))); if (!isc) v = rv; }
;             v = v * qsc; u32x2 w; w.x = cvt_pk_bf16(v[0], v[1]); w.y = cvt_pk_bf16(v[2], v[3]);
;             *(u32x2*)(QB + (size_t)row * 384 + h * 96 + cb * 16 + fq * 4) = w; }
	v_mfma_f32_16x16x32_bf16 v[74:77], v[74:77], v[2:5], 0
	v_mfma_f32_16x16x32_bf16 v[74:77], v[78:81], v[6:9], v[74:77]
	ds_read_b128 v[78:81], v0 offset:33920
	s_waitcnt lgkmcnt(0)
	v_mfma_f32_16x16x32_bf16 v[74:77], v[78:81], v[14:17], v[74:77]
	ds_read_b128 v[78:81], v0 offset:33984
	s_waitcnt lgkmcnt(0)
	v_mfma_f32_16x16x32_bf16 v[74:77], v[78:81], v[18:21], v[74:77]
	ds_read_b128 v[78:81], v0 offset:34048
	s_waitcnt lgkmcnt(0)
	v_mfma_f32_16x16x32_bf16 v[74:77], v[78:81], v[22:25], v[74:77]
	ds_read_b128 v[78:81], v0 offset:34112
	s_waitcnt lgkmcnt(0)
	v_mfma_f32_16x16x32_bf16 v[74:77], v[78:81], v[26:29], v[74:77]
	ds_read_b128 v[78:81], v0 offset:34176
	s_waitcnt lgkmcnt(0)
	v_mfma_f32_16x16x32_bf16 v[74:77], v[78:81], v[30:33], v[74:77]
	ds_read_b128 v[78:81], v0 offset:34240
	s_waitcnt lgkmcnt(0)
	v_mfma_f32_16x16x32_bf16 v[74:77], v[78:81], v[34:37], v[74:77]
	ds_read_b128 v[78:81], v0 offset:42240
	s_waitcnt lgkmcnt(0)
	v_mfma_f32_16x16x32_bf16 v[78:81], v[78:81], v[2:5], 0
	v_mfma_f32_16x16x32_bf16 v[78:81], v[130:133], v[6:9], v[78:81]
	ds_read_b128 v[130:133], v0 offset:42368
	s_waitcnt lgkmcnt(0)
	v_mfma_f32_16x16x32_bf16 v[78:81], v[130:133], v[14:17], v[78:81]
	ds_read_b128 v[130:133], v0 offset:42432
	s_waitcnt lgkmcnt(0)
	v_mfma_f32_16x16x32_bf16 v[78:81], v[130:133], v[18:21], v[78:81]
	ds_read_b128 v[130:133], v0 offset:42496
	s_waitcnt lgkmcnt(0)
	v_mfma_f32_16x16x32_bf16 v[78:81], v[130:133], v[22:25], v[78:81]
	ds_read_b128 v[130:133], v0 offset:42560
	s_waitcnt lgkmcnt(0)
	v_mfma_f32_16x16x32_bf16 v[78:81], v[130:133], v[26:29], v[78:81]
	ds_read_b128 v[130:133], v0 offset:42624
	s_waitcnt lgkmcnt(0)
	v_mfma_f32_16x16x32_bf16 v[78:81], v[130:133], v[30:33], v[78:81]
	ds_read_b128 v[130:133], v0 offset:42688
	v_mul_f32_e32 v0, v83, v83
	s_waitcnt lgkmcnt(0)
	v_mfma_f32_16x16x32_bf16 v[78:81], v[130:133], v[34:37], v[78:81]
	v_mul_f32_e32 v132, v66, v66
	v_pk_fma_f32 v[130:131], v[82:83], v[82:83], v[0:1] op_sel_hi:[1,1,0]
	v_mul_f32_e32 v0, v85, v85
	v_mov_b32_e32 v131, v132
	v_pk_fma_f32 v[132:133], v[84:85], v[84:85], v[0:1] op_sel_hi:[1,1,0]
	v_mul_f32_e32 v0, v63, v63
	v_mov_b32_e32 v133, v134
	v_pk_add_f32 v[130:131], v[130:131], v[132:133]
	v_pk_fma_f32 v[132:133], v[62:63], v[62:63], v[0:1] op_sel_hi:[1,1,0]
	v_mul_f32_e32 v0, v65, v65
	v_mov_b32_e32 v133, v135
	v_pk_fma_f32 v[134:135], v[64:65], v[64:65], v[0:1] op_sel_hi:[1,1,0]
	v_mul_f32_e32 v0, v78, v78
	v_mov_b32_e32 v135, v136
	v_pk_add_f32 v[132:133], v[132:133], v[134:135]
	v_pk_mul_f32 v[134:135], v[70:71], v[70:71]
	v_pk_add_f32 v[130:131], v[130:131], v[132:133]
	v_pk_mul_f32 v[132:133], v[72:73], v[72:73]
	v_pk_add_f32 v[130:131], v[130:131], v[130:131] op_sel:[0,1] op_sel_hi:[1,0]
	v_pk_mov_b32 v[136:137], v[134:135], v[132:133] op_sel:[1,0]
	v_mov_b32_e32 v135, v133
	v_pk_add_f32 v[132:133], v[136:137], v[134:135]
	v_mul_f32_e32 v134, v79, v79
	v_pk_add_f32 v[132:133], v[132:133], v[132:133] op_sel:[0,1] op_sel_hi:[1,0]
	v_mov_b32_e32 v131, v0
	v_mov_b32_e32 v133, v134
	v_mul_f32_e32 v0, v75, v75
	v_mul_f32_e32 v135, v80, v80
	v_pk_add_f32 v[130:131], v[130:131], v[132:133]
	v_pk_fma_f32 v[132:133], v[74:75], v[74:75], v[0:1] op_sel_hi:[1,1,0]
	v_mul_f32_e32 v0, v77, v77
	v_mul_f32_e32 v136, v81, v81
	v_mov_b32_e32 v133, v135
	v_pk_fma_f32 v[134:135], v[76:77], v[76:77], v[0:1] op_sel_hi:[1,1,0]
	s_nop 0
	v_mov_b32_e32 v135, v136
	v_pk_add_f32 v[132:133], v[132:133], v[134:135]
	s_nop 0
	v_pk_add_f32 v[130:131], v[130:131], v[132:133]
	s_nop 0
	v_add_f32_e32 v0, v130, v131
	ds_bpermute_b32 v130, v107, v0
	s_waitcnt lgkmcnt(0)
	v_add_f32_e32 v0, v0, v130
	ds_bpermute_b32 v130, v105, v0
	s_waitcnt lgkmcnt(0)
	v_add_f32_e32 v0, v0, v130
	v_fmamk_f32 v0, v0, 0x3c2aaaab, v197
	v_cmp_gt_f32_e64 s[38:39], s47, v0
	v_mul_f32_e32 v130, 0x4b800000, v0
	s_nop 0
	v_cndmask_b32_e64 v0, v0, v130, s[38:39]
	v_rsq_f32_e32 v0, v0
	s_nop 0
	v_mul_f32_e32 v130, 0x45800000, v0
	v_cndmask_b32_e64 v0, v0, v130, s[38:39]
	v_pk_mul_f32 v[132:133], v[84:85], v[0:1] op_sel_hi:[1,0]
	v_pk_mul_f32 v[134:135], v[82:83], v[0:1] op_sel_hi:[1,0]
	global_load_dwordx4 v[82:85], v[88:89], off
	v_lshl_add_u64 v[130:131], s[40:41], 0, v[108:109]
	v_pk_mul_f32 v[66:67], v[66:67], v[0:1] op_sel_hi:[1,0]
	v_pk_mul_f32 v[68:69], v[68:69], v[0:1] op_sel_hi:[1,0]
	s_waitcnt vmcnt(0)
	v_pk_mul_f32 v[82:83], v[82:83], v[134:135]
	v_pk_mul_f32 v[84:85], v[84:85], v[132:133]
	v_pk_mul_f32 v[82:83], v[82:83], s[8:9] op_sel_hi:[1,0]
	v_pk_mul_f32 v[132:133], v[84:85], s[8:9] op_sel_hi:[1,0]
	v_cvt_pk_bf16_f32 v84, v82, v83
	v_add_co_u32_e64 v82, s[38:39], s6, v130
	v_cvt_pk_bf16_f32 v85, v132, v133
	s_mov_b64 s[6:7], 0xc0
	s_nop 0
	v_addc_co_u32_e64 v83, s[38:39], 0, v131, s[38:39]
	global_store_dwordx2 v[82:83], v[84:85], off
	v_pk_mul_f32 v[84:85], v[64:65], v[0:1] op_sel_hi:[1,0]
	v_pk_mul_f32 v[130:131], v[62:63], v[0:1] op_sel_hi:[1,0]
	global_load_dwordx4 v[62:65], v[88:89], off offset:64
	v_lshl_add_u64 v[108:109], v[108:109], 0, s[6:7]
	s_waitcnt vmcnt(0)
	v_pk_mul_f32 v[62:63], v[62:63], v[130:131]
	v_pk_mul_f32 v[64:65], v[64:65], v[84:85]
	v_pk_mul_f32 v[62:63], v[62:63], s[8:9] op_sel_hi:[1,0]
	v_pk_mul_f32 v[64:65], v[64:65], s[8:9] op_sel_hi:[1,0]
	v_cvt_pk_bf16_f32 v62, v62, v63
	s_nop 0
	v_cvt_pk_bf16_f32 v63, v64, v65
	global_store_dwordx2 v[82:83], v[62:63], off offset:32
	global_load_dwordx4 v[62:65], v[88:89], off offset:128
	s_waitcnt vmcnt(0)
; #define LAS __attribute__((address_space(3)))
; __device__ __forceinline__ unsigned cvt_pk_bf16(float lo, float hi) { unsigned r; asm volatile("v_cvt_pk_bf16_f32 %0, %1, %2" : "=v"(r) : "v"(lo), "v"(hi)); return r; }
; #define MFMA16(a, b, c) __builtin_amdgcn_mfma_f32_16x16x32_bf16((a), (b), (c), 0, 0, 0)
; #define QW_LOAD(h_) do { const bf16_t* wsrc_ = WUQ + ((size_t)l * 384 + (h_) * 96) * 256; _Pragma("unroll") for (int j_ = 0; j_ < 6; ++j_) st[j_] = ld8(wsrc_ + (size_t)(tid + j_ * 512) * 8); } while (0)
; #define QW_STORE(buf_) do { _Pragma("unroll") for (int j_ = 0; j_ < 6; ++j_) { const int p_ = tid + j_ * 512; *(LAS u32x4*)(lds + (buf_) * BUF + (p_ >> 5) * RST + (p_ & 31) * 16) = st[j_]; } } while (0)
; __device__ __forceinline__ f32x4 rope16(f32x4 v, int fq, float pos) {
;     f32x4 pr; pr[0] = __shfl_xor(v[0], 32); pr[1] = __shfl_xor(v[1], 32); pr[2] = __shfl_xor(v[2], 32); pr[3] = __shfl_xor(v[3], 32);
;     f32x4 o;
; #pragma unroll
;     for (int q = 0; q < 4; ++q) { const int f = (fq * 4 + q) & 7; const float inv = __builtin_amdgcn_exp2f(-(float)f * 1.6609640474f); float sn, cs; __sincosf(pos * inv, &sn, &cs);
;         o[q] = fq < 2 ? v[q] * cs - pr[q] * sn : pr[q] * sn + v[q] * cs; }
;     return o;
; __device__ __forceinline__ void qproj_block(LAS unsigned char* lds, int bt, int l, const float* qnorm, const float* qgain, const bf16_t* P, const bf16_t* WUQ, bf16_t* QB) {
;     ...
;         QW_STORE(h & 1);
;         __syncthreads();
;         if (h < 3) QW_LOAD(h + 1);
;         const LAS unsigned char* wb = lds + (h & 1) * BUF + fr * RST + fq * 16;
;         f32x4 acc[6];
; #pragma unroll
;         for (int cb = 0; cb < 6; ++cb) { acc[cb] = (f32x4){0.f, 0.f, 0.f, 0.f};
; #pragma unroll
;             for (int ks = 0; ks < 8; ++ks) acc[cb] = MFMA16(*(const LAS bf16x8*)(wb + cb * 16 * RST + ks * 64), bfr[ks], acc[cb]); }
;     ...
;         for (int cb = 0; cb < 6; ++cb) { const f32x4 qg = *(const f32x4*)(qgain + l * 96 + cb * 16 + fq * 4); f32x4 v = acc[cb] * rh * qg;
;             if (cb >= 4) { const f32x4 rv = rope16(v, fq, (float)(cb == 4 ? (tpos >> 6) : (tpos & 63))); if (!isc) v = rv; }
;             v = v * qsc; u32x2 w; w.x = cvt_pk_bf16(v[0], v[1]); w.y = cvt_pk_bf16(v[2], v[3]);
;             *(u32x2*)(QB + (size_t)row * 384 + h * 96 + cb * 16 + fq * 4) = w; }
	v_pk_mul_f32 v[62:63], v[62:63], v[66:67]
	v_pk_mul_f32 v[64:65], v[64:65], v[68:69]
	v_pk_mul_f32 v[62:63], v[62:63], s[8:9] op_sel_hi:[1,0]
	v_pk_mul_f32 v[64:65], v[64:65], s[8:9] op_sel_hi:[1,0]
	v_cvt_pk_bf16_f32 v62, v62, v63
	v_pk_mul_f32 v[68:69], v[70:71], v[0:1] op_sel_hi:[1,0]
	v_cvt_pk_bf16_f32 v63, v64, v65
	global_store_dwordx2 v[82:83], v[62:63], off offset:64
	global_load_dwordx4 v[62:65], v[88:89], off offset:192
	v_pk_mul_f32 v[66:67], v[72:73], v[0:1] op_sel_hi:[1,0]
	s_waitcnt vmcnt(0)
	v_pk_mul_f32 v[62:63], v[62:63], v[68:69]
	v_pk_mul_f32 v[64:65], v[64:65], v[66:67]
	v_pk_mul_f32 v[62:63], v[62:63], s[8:9] op_sel_hi:[1,0]
	v_pk_mul_f32 v[64:65], v[64:65], s[8:9] op_sel_hi:[1,0]
	v_cvt_pk_bf16_f32 v62, v62, v63
	v_pk_mul_f32 v[66:67], v[74:75], v[0:1] op_sel_hi:[1,0]
	v_cvt_pk_bf16_f32 v63, v64, v65
	global_store_dwordx2 v[82:83], v[62:63], off offset:96
	global_load_dwordx4 v[62:65], v[88:89], off offset:256
	v_pk_mul_f32 v[68:69], v[76:77], v[0:1] op_sel_hi:[1,0]
	s_waitcnt vmcnt(0)
	v_pk_mul_f32 v[62:63], v[66:67], v[62:63]
	v_pk_mul_f32 v[64:65], v[68:69], v[64:65]
	ds_bpermute_b32 v66, v105, v62
	ds_bpermute_b32 v67, v105, v63
	ds_bpermute_b32 v68, v105, v64
	ds_bpermute_b32 v69, v105, v65
	s_waitcnt lgkmcnt(0)
	v_pk_mul_f32 v[66:67], v[100:101], v[66:67]
	s_nop 0
	v_cndmask_b32_e64 v67, v67, -v67, s[36:37]
	v_pk_mul_f32 v[68:69], v[102:103], v[68:69]
	v_cndmask_b32_e64 v66, v66, -v66, s[36:37]
	v_cndmask_b32_e64 v69, v69, -v69, s[36:37]
	v_cndmask_b32_e64 v68, v68, -v68, s[36:37]
	v_pk_fma_f32 v[66:67], v[96:97], v[62:63], v[66:67]
	v_pk_fma_f32 v[68:69], v[98:99], v[64:65], v[68:69]
	v_cndmask_b32_e32 v63, v67, v63, vcc
	v_cndmask_b32_e32 v62, v66, v62, vcc
	v_cndmask_b32_e32 v65, v69, v65, vcc
	v_cndmask_b32_e32 v64, v68, v64, vcc
	v_pk_mul_f32 v[62:63], v[62:63], s[8:9] op_sel_hi:[1,0]
	v_pk_mul_f32 v[64:65], v[64:65], s[8:9] op_sel_hi:[1,0]
	v_cvt_pk_bf16_f32 v62, v62, v63
	v_pk_mul_f32 v[66:67], v[78:79], v[0:1] op_sel_hi:[1,0]
	v_cvt_pk_bf16_f32 v63, v64, v65
	global_store_dwordx2 v[82:83], v[62:63], off offset:128
	global_load_dwordx4 v[62:65], v[88:89], off offset:320
	v_pk_mul_f32 v[68:69], v[80:81], v[0:1] op_sel_hi:[1,0]
	s_waitcnt vmcnt(0)
	v_pk_mul_f32 v[62:63], v[66:67], v[62:63]
	v_pk_mul_f32 v[64:65], v[68:69], v[64:65]
	ds_bpermute_b32 v66, v105, v62
	ds_bpermute_b32 v67, v105, v63
	ds_bpermute_b32 v68, v105, v64
	ds_bpermute_b32 v69, v105, v65
	s_waitcnt lgkmcnt(0)
	v_pk_mul_f32 v[66:67], v[90:91], v[66:67]
	s_nop 0
	v_cndmask_b32_e64 v67, v67, -v67, s[36:37]
	v_pk_mul_f32 v[68:69], v[94:95], v[68:69]
	v_cndmask_b32_e64 v66, v66, -v66, s[36:37]
	v_cndmask_b32_e64 v69, v69, -v69, s[36:37]
	v_cndmask_b32_e64 v68, v68, -v68, s[36:37]
	v_pk_fma_f32 v[66:67], v[86:87], v[62:63], v[66:67]
	v_pk_fma_f32 v[68:69], v[92:93], v[64:65], v[68:69]
	v_cndmask_b32_e32 v63, v67, v63, vcc
	v_cndmask_b32_e32 v62, v66, v62, vcc
	v_cndmask_b32_e32 v65, v69, v65, vcc
	v_cndmask_b32_e32 v64, v68, v64, vcc
	v_pk_mul_f32 v[62:63], v[62:63], s[8:9] op_sel_hi:[1,0]
	v_pk_mul_f32 v[64:65], v[64:65], s[8:9] op_sel_hi:[1,0]
	v_cvt_pk_bf16_f32 v62, v62, v63
	s_nop 0
	v_cvt_pk_bf16_f32 v63, v64, v65
	global_store_dwordx2 v[82:83], v[62:63], off offset:160
	s_cbranch_scc1 .LBB0_417
	v_mov_b64_e32 v[62:63], s[42:43]
	v_mad_i64_i32 v[62:63], s[6:7], v104, s50, v[62:63]
	v_lshlrev_b32_e32 v0, 1, v106
	v_lshl_add_u64 v[62:63], v[62:63], 0, v[0:1]
	v_add_u32_e32 v0, v123, v124
	ds_write_b128 v0, v[58:61] offset:50688
	v_add_u32_e32 v0, v123, v125
	ds_write_b128 v0, v[54:57] offset:50688
	v_add_u32_e32 v0, v123, v126
	ds_write_b128 v0, v[50:53] offset:50688
	v_add_u32_e32 v0, v123, v127
	ds_write_b128 v0, v[46:49] offset:50688
	v_add_u32_e32 v0, v123, v128
	ds_write_b128 v0, v[42:45] offset:50688
	v_add_u32_e32 v0, v123, v129
	ds_write_b128 v0, v[38:41] offset:50688
	s_waitcnt lgkmcnt(0)
	s_barrier
	ds_read_b128 v[38:41], v122 offset:50688
	ds_read_b128 v[42:45], v122 offset:50752
	s_waitcnt lgkmcnt(0)
	v_mfma_f32_16x16x32_bf16 v[38:41], v[38:41], v[2:5], 0
	v_add_u32_e32 v0, 0x10800, v122
	v_readlane_b32 s1, v253, 42
	s_add_i32 s5, s5, s74
	v_mfma_f32_16x16x32_bf16 v[38:41], v[42:45], v[6:9], v[38:41]
	ds_read_b128 v[42:45], v122 offset:50816
	s_add_i32 s4, s4, s1
	v_readlane_b32 s1, v254, 37
	s_waitcnt lgkmcnt(0)
	v_mfma_f32_16x16x32_bf16 v[38:41], v[42:45], v[14:17], v[38:41]
	ds_read_b128 v[42:45], v122 offset:50880
	s_cmp_ge_i32 s5, s1
	s_waitcnt lgkmcnt(0)
	v_mfma_f32_16x16x32_bf16 v[38:41], v[42:45], v[18:21], v[38:41]
	ds_read_b128 v[42:45], v122 offset:50944
	s_waitcnt lgkmcnt(0)
	v_mfma_f32_16x16x32_bf16 v[38:41], v[42:45], v[22:25], v[38:41]
	ds_read_b128 v[42:45], v122 offset:51008
	s_waitcnt lgkmcnt(0)
	v_mfma_f32_16x16x32_bf16 v[38:41], v[42:45], v[26:29], v[38:41]
	ds_read_b128 v[42:45], v122 offset:51072
	s_waitcnt lgkmcnt(0)
	v_mfma_f32_16x16x32_bf16 v[38:41], v[42:45], v[30:33], v[38:41]
	ds_read_b128 v[42:45], v122 offset:51136
	s_waitcnt lgkmcnt(0)
	v_mfma_f32_16x16x32_bf16 v[54:57], v[42:45], v[34:37], v[38:41]
	s_nop 4
	ds_read_b128 v[38:41], v122 offset:59136
	ds_read_b128 v[42:45], v122 offset:59200
	s_waitcnt lgkmcnt(0)
	v_mfma_f32_16x16x32_bf16 v[38:41], v[38:41], v[2:5], 0
	v_mfma_f32_16x16x32_bf16 v[38:41], v[42:45], v[6:9], v[38:41]
	ds_read_b128 v[42:45], v122 offset:59264
	s_waitcnt lgkmcnt(0)
	v_mfma_f32_16x16x32_bf16 v[38:41], v[42:45], v[14:17], v[38:41]
	ds_read_b128 v[42:45], v122 offset:59328
	s_waitcnt lgkmcnt(0)
	v_mfma_f32_16x16x32_bf16 v[38:41], v[42:45], v[18:21], v[38:41]
	ds_read_b128 v[42:45], v122 offset:59392
	s_waitcnt lgkmcnt(0)
; #define LAS __attribute__((address_space(3)))
; #define MFMA16(a, b, c) __builtin_amdgcn_mfma_f32_16x16x32_bf16((a), (b), (c), 0, 0, 0)
; __device__ __forceinline__ void qproj_block(LAS unsigned char* lds, int bt, int l, const float* qnorm, const float* qgain, const bf16_t* P, const bf16_t* WUQ, bf16_t* QB) {
;     ...
;         for (int cb = 0; cb < 6; ++cb) { acc[cb] = (f32x4){0.f, 0.f, 0.f, 0.f};
; #pragma unroll
;             for (int ks = 0; ks < 8; ++ks) acc[cb] = MFMA16(*(const LAS bf16x8*)(wb + cb * 16 * RST + ks * 64), bfr[ks], acc[cb]); }
	v_mfma_f32_16x16x32_bf16 v[38:41], v[42:45], v[22:25], v[38:41]
	ds_read_b128 v[42:45], v122 offset:59456
	s_waitcnt lgkmcnt(0)
	v_mfma_f32_16x16x32_bf16 v[38:41], v[42:45], v[26:29], v[38:41]
	ds_read_b128 v[42:45], v122 offset:59520
	s_waitcnt lgkmcnt(0)
	v_mfma_f32_16x16x32_bf16 v[38:41], v[42:45], v[30:33], v[38:41]
	ds_read_b128 v[42:45], v122 offset:59584
	s_waitcnt lgkmcnt(0)
	v_mfma_f32_16x16x32_bf16 v[38:41], v[42:45], v[34:37], v[38:41]
	ds_read_b128 v[42:45], v0
	v_add_u32_e32 v0, 0x10840, v122
	ds_read_b128 v[46:49], v0
	s_waitcnt lgkmcnt(0)
	v_mfma_f32_16x16x32_bf16 v[42:45], v[42:45], v[2:5], 0
	v_add_u32_e32 v0, 0x10880, v122
	v_mfma_f32_16x16x32_bf16 v[42:45], v[46:49], v[6:9], v[42:45]
	ds_read_b128 v[46:49], v0
	v_add_u32_e32 v0, 0x108c0, v122
	s_waitcnt lgkmcnt(0)
	v_mfma_f32_16x16x32_bf16 v[42:45], v[46:49], v[14:17], v[42:45]
	ds_read_b128 v[46:49], v0
	v_add_u32_e32 v0, 0x10900, v122
	s_waitcnt lgkmcnt(0)
	v_mfma_f32_16x16x32_bf16 v[42:45], v[46:49], v[18:21], v[42:45]
	ds_read_b128 v[46:49], v0
	v_add_u32_e32 v0, 0x10940, v122
	s_waitcnt lgkmcnt(0)
	v_mfma_f32_16x16x32_bf16 v[42:45], v[46:49], v[22:25], v[42:45]
	ds_read_b128 v[46:49], v0
	v_add_u32_e32 v0, 0x10980, v122
	s_waitcnt lgkmcnt(0)
	v_mfma_f32_16x16x32_bf16 v[42:45], v[46:49], v[26:29], v[42:45]
	ds_read_b128 v[46:49], v0
	v_add_u32_e32 v0, 0x109c0, v122
	s_waitcnt lgkmcnt(0)
	v_mfma_f32_16x16x32_bf16 v[42:45], v[46:49], v[30:33], v[42:45]
	ds_read_b128 v[46:49], v0
	v_add_u32_e32 v0, 0x12900, v122
	s_waitcnt lgkmcnt(0)
	v_mfma_f32_16x16x32_bf16 v[42:45], v[46:49], v[34:37], v[42:45]
	ds_read_b128 v[46:49], v0
	v_add_u32_e32 v0, 0x12940, v122
	ds_read_b128 v[50:53], v0
	s_waitcnt lgkmcnt(0)
	v_mfma_f32_16x16x32_bf16 v[46:49], v[46:49], v[2:5], 0
	v_add_u32_e32 v0, 0x12980, v122
	v_mfma_f32_16x16x32_bf16 v[46:49], v[50:53], v[6:9], v[46:49]
	ds_read_b128 v[50:53], v0
	v_add_u32_e32 v0, 0x129c0, v122
	s_waitcnt lgkmcnt(0)
	v_mfma_f32_16x16x32_bf16 v[46:49], v[50:53], v[14:17], v[46:49]
	ds_read_b128 v[50:53], v0
	v_add_u32_e32 v0, 0x12a00, v122
	s_waitcnt lgkmcnt(0)
	v_mfma_f32_16x16x32_bf16 v[46:49], v[50:53], v[18:21], v[46:49]
	ds_read_b128 v[50:53], v0
	v_add_u32_e32 v0, 0x12a40, v122
	s_waitcnt lgkmcnt(0)
	v_mfma_f32_16x16x32_bf16 v[46:49], v[50:53], v[22:25], v[46:49]
	ds_read_b128 v[50:53], v0
	v_add_u32_e32 v0, 0x12a80, v122
	s_waitcnt lgkmcnt(0)
	v_mfma_f32_16x16x32_bf16 v[46:49], v[50:53], v[26:29], v[46:49]
	ds_read_b128 v[50:53], v0
	v_add_u32_e32 v0, 0x12ac0, v122
	s_waitcnt lgkmcnt(0)
	v_mfma_f32_16x16x32_bf16 v[46:49], v[50:53], v[30:33], v[46:49]
	ds_read_b128 v[50:53], v0
	v_add_u32_e32 v0, 0x14a00, v122
	s_waitcnt lgkmcnt(0)
	v_mfma_f32_16x16x32_bf16 v[46:49], v[50:53], v[34:37], v[46:49]
	ds_read_b128 v[50:53], v0
	v_add_u32_e32 v0, 0x14a40, v122
	ds_read_b128 v[58:61], v0
	s_waitcnt lgkmcnt(0)
	v_mfma_f32_16x16x32_bf16 v[50:53], v[50:53], v[2:5], 0
	v_add_u32_e32 v0, 0x14a80, v122
	v_mfma_f32_16x16x32_bf16 v[50:53], v[58:61], v[6:9], v[50:53]
	ds_read_b128 v[58:61], v0
	v_add_u32_e32 v0, 0x14ac0, v122
	s_waitcnt lgkmcnt(0)
	v_mfma_f32_16x16x32_bf16 v[50:53], v[58:61], v[14:17], v[50:53]
	ds_read_b128 v[58:61], v0
	v_add_u32_e32 v0, 0x14b00, v122
	s_waitcnt lgkmcnt(0)
	v_mfma_f32_16x16x32_bf16 v[50:53], v[58:61], v[18:21], v[50:53]
	ds_read_b128 v[58:61], v0
	v_add_u32_e32 v0, 0x14b40, v122
	s_waitcnt lgkmcnt(0)
	v_mfma_f32_16x16x32_bf16 v[50:53], v[58:61], v[22:25], v[50:53]
	ds_read_b128 v[58:61], v0
	v_add_u32_e32 v0, 0x14b80, v122
	s_waitcnt lgkmcnt(0)
	v_mfma_f32_16x16x32_bf16 v[50:53], v[58:61], v[26:29], v[50:53]
	ds_read_b128 v[58:61], v0
	v_add_u32_e32 v0, 0x14bc0, v122
	s_waitcnt lgkmcnt(0)
	v_mfma_f32_16x16x32_bf16 v[50:53], v[58:61], v[30:33], v[50:53]
	ds_read_b128 v[58:61], v0
	v_add_u32_e32 v0, 0x16b00, v122
	s_waitcnt lgkmcnt(0)
	v_mfma_f32_16x16x32_bf16 v[50:53], v[58:61], v[34:37], v[50:53]
	ds_read_b128 v[58:61], v0
	v_add_u32_e32 v0, 0x16b40, v122
	s_waitcnt lgkmcnt(0)
	v_mfma_f32_16x16x32_bf16 v[2:5], v[58:61], v[2:5], 0
	ds_read_b128 v[58:61], v0
	v_add_u32_e32 v0, 0x16b80, v122
	s_waitcnt lgkmcnt(0)
	v_mfma_f32_16x16x32_bf16 v[2:5], v[58:61], v[6:9], v[2:5]
	ds_read_b128 v[6:9], v0
	v_add_u32_e32 v0, 0x16bc0, v122
	s_waitcnt lgkmcnt(0)
	v_mfma_f32_16x16x32_bf16 v[2:5], v[6:9], v[14:17], v[2:5]
	ds_read_b128 v[6:9], v0
	v_add_u32_e32 v0, 0x16c00, v122
	v_mul_f32_e32 v14, v43, v43
	s_waitcnt lgkmcnt(0)
	v_mfma_f32_16x16x32_bf16 v[2:5], v[6:9], v[18:21], v[2:5]
	ds_read_b128 v[6:9], v0
	v_add_u32_e32 v0, 0x16c40, v122
	v_mul_f32_e32 v15, v44, v44
	s_waitcnt lgkmcnt(0)
	v_mfma_f32_16x16x32_bf16 v[2:5], v[6:9], v[22:25], v[2:5]
	ds_read_b128 v[6:9], v0
	v_add_u32_e32 v0, 0x16c80, v122
	v_mul_f32_e32 v16, v45, v45
	s_waitcnt lgkmcnt(0)
	v_mfma_f32_16x16x32_bf16 v[2:5], v[6:9], v[26:29], v[2:5]
	ds_read_b128 v[6:9], v0
	v_add_u32_e32 v0, 0x16cc0, v122
	s_waitcnt lgkmcnt(0)
	v_mfma_f32_16x16x32_bf16 v[2:5], v[6:9], v[30:33], v[2:5]
	ds_read_b128 v[6:9], v0
	v_mul_f32_e32 v0, v55, v55
	s_waitcnt lgkmcnt(0)
; __device__ __forceinline__ unsigned cvt_pk_bf16(float lo, float hi) { unsigned r; asm volatile("v_cvt_pk_bf16_f32 %0, %1, %2" : "=v"(r) : "v"(lo), "v"(hi)); return r; }
; __device__ __forceinline__ void qproj_block(LAS unsigned char* lds, int bt, int l, const float* qnorm, const float* qgain, const bf16_t* P, const bf16_t* WUQ, bf16_t* QB) {
;     ...
;         float s2 = 0.f;
; #pragma unroll
;         for (int cb = 0; cb < 6; ++cb) s2 += (acc[cb][0] * acc[cb][0] + acc[cb][1] * acc[cb][1]) + (acc[cb][2] * acc[cb][2] + acc[cb][3] * acc[cb][3]);
;         s2 += __shfl_xor(s2, 16); s2 += __shfl_xor(s2, 32);
;         const float rh = rsqrtf(s2 * (1.f / 96.f) + EPS);
; #pragma unroll
;         for (int cb = 0; cb < 6; ++cb) { const f32x4 qg = *(const f32x4*)(qgain + l * 96 + cb * 16 + fq * 4); f32x4 v = acc[cb] * rh * qg;
;             if (cb >= 4) { const f32x4 rv = rope16(v, fq, (float)(cb == 4 ? (tpos >> 6) : (tpos & 63))); if (!isc) v = rv; }
;             v = v * qsc; u32x2 w; w.x = cvt_pk_bf16(v[0], v[1]); w.y = cvt_pk_bf16(v[2], v[3]);
;             *(u32x2*)(QB + (size_t)row * 384 + h * 96 + cb * 16 + fq * 4) = w; }
;     }
;     ...
;     __syncthreads();
	v_mfma_f32_16x16x32_bf16 v[2:5], v[6:9], v[34:37], v[2:5]
	v_mul_f32_e32 v8, v42, v42
	v_pk_fma_f32 v[6:7], v[54:55], v[54:55], v[0:1] op_sel_hi:[1,1,0]
	v_mul_f32_e32 v0, v57, v57
	v_mov_b32_e32 v7, v8
	v_pk_fma_f32 v[8:9], v[56:57], v[56:57], v[0:1] op_sel_hi:[1,1,0]
	v_mul_f32_e32 v0, v39, v39
	v_mov_b32_e32 v9, v14
	v_pk_add_f32 v[6:7], v[6:7], v[8:9]
	v_pk_fma_f32 v[8:9], v[38:39], v[38:39], v[0:1] op_sel_hi:[1,1,0]
	v_mul_f32_e32 v0, v41, v41
	v_mov_b32_e32 v9, v15
	v_pk_fma_f32 v[14:15], v[40:41], v[40:41], v[0:1] op_sel_hi:[1,1,0]
	v_mul_f32_e32 v0, v2, v2
	v_mov_b32_e32 v15, v16
	v_pk_add_f32 v[8:9], v[8:9], v[14:15]
	v_pk_mul_f32 v[14:15], v[46:47], v[46:47]
	v_pk_add_f32 v[6:7], v[6:7], v[8:9]
	v_pk_mul_f32 v[8:9], v[48:49], v[48:49]
	v_pk_add_f32 v[6:7], v[6:7], v[6:7] op_sel:[0,1] op_sel_hi:[1,0]
	v_pk_mov_b32 v[16:17], v[14:15], v[8:9] op_sel:[1,0]
	v_mov_b32_e32 v15, v9
	v_pk_add_f32 v[8:9], v[16:17], v[14:15]
	v_mul_f32_e32 v14, v3, v3
	v_pk_add_f32 v[8:9], v[8:9], v[8:9] op_sel:[0,1] op_sel_hi:[1,0]
	v_mov_b32_e32 v7, v0
	v_mov_b32_e32 v9, v14
	v_mul_f32_e32 v0, v51, v51
	v_mul_f32_e32 v15, v4, v4
	v_pk_add_f32 v[6:7], v[6:7], v[8:9]
	v_pk_fma_f32 v[8:9], v[50:51], v[50:51], v[0:1] op_sel_hi:[1,1,0]
	v_mul_f32_e32 v0, v53, v53
	v_mul_f32_e32 v16, v5, v5
	v_mov_b32_e32 v9, v15
	v_pk_fma_f32 v[14:15], v[52:53], v[52:53], v[0:1] op_sel_hi:[1,1,0]
	s_nop 0
	v_mov_b32_e32 v15, v16
	v_pk_add_f32 v[8:9], v[8:9], v[14:15]
	s_nop 0
	v_pk_add_f32 v[6:7], v[6:7], v[8:9]
	s_nop 0
	v_add_f32_e32 v0, v6, v7
	ds_bpermute_b32 v6, v107, v0
	s_waitcnt lgkmcnt(0)
	v_add_f32_e32 v0, v0, v6
	ds_bpermute_b32 v6, v105, v0
	s_waitcnt lgkmcnt(0)
	v_add_f32_e32 v0, v0, v6
	v_fmamk_f32 v0, v0, 0x3c2aaaab, v197
	v_cmp_gt_f32_e64 s[38:39], s47, v0
	v_mul_f32_e32 v6, 0x4b800000, v0
	s_nop 0
	v_cndmask_b32_e64 v0, v0, v6, s[38:39]
	v_rsq_f32_e32 v0, v0
	s_nop 0
	v_mul_f32_e32 v6, 0x45800000, v0
	v_cndmask_b32_e64 v0, v0, v6, s[38:39]
	global_load_dwordx4 v[6:9], v[88:89], off
	v_pk_mul_f32 v[16:17], v[54:55], v[0:1] op_sel_hi:[1,0]
	v_pk_mul_f32 v[14:15], v[56:57], v[0:1] op_sel_hi:[1,0]
	s_waitcnt vmcnt(0)
	v_pk_mul_f32 v[6:7], v[6:7], v[16:17]
	v_pk_mul_f32 v[8:9], v[8:9], v[14:15]
	v_pk_mul_f32 v[6:7], v[6:7], s[8:9] op_sel_hi:[1,0]
	v_pk_mul_f32 v[8:9], v[8:9], s[8:9] op_sel_hi:[1,0]
	v_cvt_pk_bf16_f32 v6, v6, v7
	v_pk_mul_f32 v[16:17], v[38:39], v[0:1] op_sel_hi:[1,0]
	v_cvt_pk_bf16_f32 v7, v8, v9
	global_store_dwordx2 v[62:63], v[6:7], off offset:576
	global_load_dwordx4 v[6:9], v[88:89], off offset:64
	v_pk_mul_f32 v[14:15], v[40:41], v[0:1] op_sel_hi:[1,0]
	s_waitcnt vmcnt(0)
	v_pk_mul_f32 v[6:7], v[6:7], v[16:17]
	v_pk_mul_f32 v[8:9], v[8:9], v[14:15]
	v_pk_mul_f32 v[6:7], v[6:7], s[8:9] op_sel_hi:[1,0]
	v_pk_mul_f32 v[8:9], v[8:9], s[8:9] op_sel_hi:[1,0]
	v_cvt_pk_bf16_f32 v6, v6, v7
	v_pk_mul_f32 v[16:17], v[42:43], v[0:1] op_sel_hi:[1,0]
	v_cvt_pk_bf16_f32 v7, v8, v9
	global_store_dwordx2 v[62:63], v[6:7], off offset:608
	global_load_dwordx4 v[6:9], v[88:89], off offset:128
	v_pk_mul_f32 v[14:15], v[44:45], v[0:1] op_sel_hi:[1,0]
	s_waitcnt vmcnt(0)
	v_pk_mul_f32 v[6:7], v[6:7], v[16:17]
	v_pk_mul_f32 v[8:9], v[8:9], v[14:15]
	v_pk_mul_f32 v[6:7], v[6:7], s[8:9] op_sel_hi:[1,0]
	v_pk_mul_f32 v[8:9], v[8:9], s[8:9] op_sel_hi:[1,0]
	v_cvt_pk_bf16_f32 v6, v6, v7
	v_pk_mul_f32 v[16:17], v[46:47], v[0:1] op_sel_hi:[1,0]
	v_cvt_pk_bf16_f32 v7, v8, v9
	global_store_dwordx2 v[62:63], v[6:7], off offset:640
	global_load_dwordx4 v[6:9], v[88:89], off offset:192
	v_pk_mul_f32 v[14:15], v[48:49], v[0:1] op_sel_hi:[1,0]
	s_waitcnt vmcnt(0)
	v_pk_mul_f32 v[6:7], v[6:7], v[16:17]
	v_pk_mul_f32 v[8:9], v[8:9], v[14:15]
	v_pk_mul_f32 v[6:7], v[6:7], s[8:9] op_sel_hi:[1,0]
	v_pk_mul_f32 v[8:9], v[8:9], s[8:9] op_sel_hi:[1,0]
	v_cvt_pk_bf16_f32 v6, v6, v7
	v_pk_mul_f32 v[14:15], v[50:51], v[0:1] op_sel_hi:[1,0]
	v_cvt_pk_bf16_f32 v7, v8, v9
	global_store_dwordx2 v[62:63], v[6:7], off offset:672
	global_load_dwordx4 v[6:9], v[88:89], off offset:256
	v_pk_mul_f32 v[16:17], v[52:53], v[0:1] op_sel_hi:[1,0]
	s_waitcnt vmcnt(0)
	v_pk_mul_f32 v[6:7], v[14:15], v[6:7]
	v_pk_mul_f32 v[8:9], v[16:17], v[8:9]
	ds_bpermute_b32 v14, v105, v6
	ds_bpermute_b32 v15, v105, v7
	ds_bpermute_b32 v16, v105, v8
	ds_bpermute_b32 v17, v105, v9
	s_waitcnt lgkmcnt(0)
	v_pk_mul_f32 v[14:15], v[100:101], v[14:15]
	s_nop 0
	v_cndmask_b32_e64 v15, v15, -v15, s[36:37]
	v_pk_mul_f32 v[16:17], v[102:103], v[16:17]
	v_cndmask_b32_e64 v14, v14, -v14, s[36:37]
	v_cndmask_b32_e64 v17, v17, -v17, s[36:37]
	v_cndmask_b32_e64 v16, v16, -v16, s[36:37]
	v_pk_fma_f32 v[14:15], v[96:97], v[6:7], v[14:15]
	v_pk_fma_f32 v[16:17], v[98:99], v[8:9], v[16:17]
	v_cndmask_b32_e32 v7, v15, v7, vcc
	v_cndmask_b32_e32 v6, v14, v6, vcc
	v_cndmask_b32_e32 v9, v17, v9, vcc
	v_cndmask_b32_e32 v8, v16, v8, vcc
	v_pk_mul_f32 v[6:7], v[6:7], s[8:9] op_sel_hi:[1,0]
	v_pk_mul_f32 v[8:9], v[8:9], s[8:9] op_sel_hi:[1,0]
	v_cvt_pk_bf16_f32 v6, v6, v7
	s_nop 0
	v_cvt_pk_bf16_f32 v7, v8, v9
	global_store_dwordx2 v[62:63], v[6:7], off offset:704
	v_pk_mul_f32 v[6:7], v[2:3], v[0:1] op_sel_hi:[1,0]
	v_pk_mul_f32 v[8:9], v[4:5], v[0:1] op_sel_hi:[1,0]
	global_load_dwordx4 v[2:5], v[88:89], off offset:320
	s_waitcnt vmcnt(0)
	v_pk_mul_f32 v[2:3], v[6:7], v[2:3]
	v_pk_mul_f32 v[4:5], v[8:9], v[4:5]
	ds_bpermute_b32 v6, v105, v2
	ds_bpermute_b32 v7, v105, v3
	ds_bpermute_b32 v8, v105, v4
	ds_bpermute_b32 v9, v105, v5
	s_waitcnt lgkmcnt(0)
	v_pk_mul_f32 v[6:7], v[90:91], v[6:7]
	s_nop 0
	v_cndmask_b32_e64 v7, v7, -v7, s[36:37]
	v_pk_mul_f32 v[8:9], v[94:95], v[8:9]
	v_cndmask_b32_e64 v6, v6, -v6, s[36:37]
	v_cndmask_b32_e64 v9, v9, -v9, s[36:37]
	v_cndmask_b32_e64 v8, v8, -v8, s[36:37]
	v_pk_fma_f32 v[6:7], v[86:87], v[2:3], v[6:7]
	v_pk_fma_f32 v[8:9], v[92:93], v[4:5], v[8:9]
	v_cndmask_b32_e32 v3, v7, v3, vcc
	v_cndmask_b32_e32 v2, v6, v2, vcc
	v_cndmask_b32_e32 v5, v9, v5, vcc
	v_cndmask_b32_e32 v4, v8, v4, vcc
	v_pk_mul_f32 v[2:3], v[2:3], s[8:9] op_sel_hi:[1,0]
	v_pk_mul_f32 v[4:5], v[4:5], s[8:9] op_sel_hi:[1,0]
	v_cvt_pk_bf16_f32 v2, v2, v3
	s_nop 0
	v_cvt_pk_bf16_f32 v3, v4, v5
	global_store_dwordx2 v[62:63], v[2:3], off offset:736
	s_waitcnt lgkmcnt(0)
	s_barrier
	s_cbranch_scc0 .LBB0_416

; __device__ __forceinline__ unsigned cvt_pk_bf16(float lo, float hi) { unsigned r; asm volatile("v_cvt_pk_bf16_f32 %0, %1, %2" : "=v"(r) : "v"(lo), "v"(hi)); return r; }
; __device__ __forceinline__ float bflo(unsigned w) { return __uint_as_float(w << 16); }
; __device__ __forceinline__ float bfhi(unsigned w) { return __uint_as_float(w & 0xffff0000u); }
; #define UNPK8(VV_, XX_) float XX_[8] = {bflo((VV_).x), bfhi((VV_).x), bflo((VV_).y), bfhi((VV_).y), bflo((VV_).z), bfhi((VV_).z), bflo((VV_).w), bfhi((VV_).w)}
; __device__ __forceinline__ void kvproj_task(int t, int l, const float* kvnorm, const float* kgain, const bf16_t* P, const bf16_t* WUKV, bf16_t* KB, bf16_t* VT, int fr, int fq) {
;     const int h = t & 3, row0 = (t >> 2) * 32 + fr; const bool isc = row0 >= ML;
;     bf16x8 bfr[2][4]; f32x4 kr[2][2]; float skr[2];
; #pragma unroll
;     for (int tb = 0; tb < 2; ++tb) { const int row = row0 + tb * 16; float ss = 0.f; u32x4 raw[4];
; #pragma unroll
;         for (int ks = 0; ks < 4; ++ks) { raw[ks] = ld8(P + (size_t)row * INP + ks * 32 + fq * 8); UNPK8(raw[ks], x);
;             ss += (x[0] * x[0] + x[1] * x[1]) + (x[2] * x[2] + x[3] * x[3]) + (x[4] * x[4] + x[5] * x[5]) + (x[6] * x[6] + x[7] * x[7]); }
; #pragma unroll
;         for (int cbr = 0; cbr < 2; ++cbr) { const u32x2 w = ld4(P + (size_t)row * INP + OFF_KROPE + cbr * 16 + fq * 4); kr[tb][cbr] = (f32x4){bflo(w.x), bfhi(w.x), bflo(w.y), bfhi(w.y)}; }
;         ss += __shfl_xor(ss, 16); ss += __shfl_xor(ss, 32);
;         const float rinv = rsqrtf(ss * (1.f / 128.f) + EPS);
; #pragma unroll
;         for (int ks = 0; ks < 4; ++ks) { const float* gp = kvnorm + l * 128 + ks * 32 + fq * 8; const f32x4 g0 = *(const f32x4*)gp, g1 = *(const f32x4*)(gp + 4); UNPK8(raw[ks], x); u32x4 o;
;             o.x = cvt_pk_bf16(x[0] * rinv * g0[0], x[1] * rinv * g0[1]); o.y = cvt_pk_bf16(x[2] * rinv * g0[2], x[3] * rinv * g0[3]);
;             o.z = cvt_pk_bf16(x[4] * rinv * g1[0], x[5] * rinv * g1[1]); o.w = cvt_pk_bf16(x[6] * rinv * g1[2], x[7] * rinv * g1[3]);
;             bfr[tb][ks] = asfrag(o); }
.LBB0_422:
	s_and_b32 s1, s4, 0xffffffe0
	v_or_b32_e32 v171, s1, v97
	v_mad_i64_i32 v[6:7], s[6:7], v171, s84, v[94:95]
	global_load_dwordx4 v[14:17], v[6:7], off
	global_load_dwordx4 v[2:5], v[6:7], off offset:64
	global_load_dwordx4 v[40:43], v[6:7], off offset:128
	global_load_dwordx4 v[50:53], v[6:7], off offset:192
	v_or_b32_e32 v173, 16, v171
	s_add_i32 s5, s5, s60
	s_add_i32 s4, s4, s75
	s_cmpk_gt_i32 s5, 0x8ff
	s_waitcnt vmcnt(0) lgkmcnt(0)
	v_and_b32_e32 v37, 0xffff0000, v15
	v_and_b32_e32 v25, 0xffff0000, v3
	v_and_b32_e32 v24, 0xffff0000, v2
	v_lshlrev_b32_e32 v27, 16, v3
	v_lshlrev_b32_e32 v26, 16, v2
	v_pk_mul_f32 v[2:3], v[24:25], v[24:25]
	v_and_b32_e32 v21, 0xffff0000, v5
	v_and_b32_e32 v20, 0xffff0000, v4
	v_pk_fma_f32 v[2:3], v[26:27], v[26:27], v[2:3]
	v_lshlrev_b32_e32 v23, 16, v5
	v_lshlrev_b32_e32 v22, 16, v4
	v_pk_mul_f32 v[4:5], v[20:21], v[20:21]
	v_pk_add_f32 v[2:3], v[2:3], v[2:3] op_sel:[0,1] op_sel_hi:[1,0]
	v_pk_fma_f32 v[34:35], v[22:23], v[22:23], v[4:5]
	v_and_b32_e32 v39, 0xffff0000, v14
	v_pk_add_f32 v[44:45], v[34:35], v[2:3]
	v_mad_i64_i32 v[2:3], s[6:7], v171, s84, v[168:169]
	global_load_dwordx2 v[4:5], v[2:3], off offset:256
	s_nop 0
	global_load_dwordx2 v[2:3], v[2:3], off offset:288
	v_and_b32_e32 v38, 0xffff0000, v16
	v_lshlrev_b32_e32 v36, 16, v15
	v_mul_f32_e32 v0, v37, v37
	v_lshlrev_b32_e32 v18, 16, v40
	v_and_b32_e32 v19, 0xffff0000, v40
	v_lshlrev_b32_e32 v8, 16, v41
	v_and_b32_e32 v9, 0xffff0000, v41
	v_lshlrev_b32_e32 v41, 16, v14
	v_lshlrev_b32_e32 v40, 16, v16
	v_pk_mul_f32 v[14:15], v[38:39], v[38:39]
	v_pk_fma_f32 v[28:29], v[36:37], v[36:37], v[0:1] op_sel_hi:[1,1,0]
	v_lshlrev_b32_e32 v7, 16, v53
	v_pk_fma_f32 v[14:15], v[40:41], v[40:41], v[14:15]
	v_mul_f32_e32 v6, v19, v19
	v_lshlrev_b32_e32 v32, 16, v17
	v_and_b32_e32 v33, 0xffff0000, v17
	v_lshlrev_b32_e32 v48, 16, v51
	v_and_b32_e32 v47, 0xffff0000, v51
	v_pk_add_f32 v[16:17], v[14:15], v[28:29] op_sel:[1,0] op_sel_hi:[0,1]
	v_lshlrev_b32_e32 v31, 16, v50
	v_and_b32_e32 v29, 0xffff0000, v50
	v_pk_fma_f32 v[50:51], v[18:19], v[18:19], v[6:7] op_sel_hi:[1,1,0]
	v_mul_f32_e32 v6, v9, v9
	v_and_b32_e32 v0, 0xffff0000, v53
	v_mul_f32_e32 v46, v48, v48
	v_mul_f32_e32 v49, v47, v47
	v_pk_add_f32 v[54:55], v[14:15], v[16:17]
	v_and_b32_e32 v28, 0xffff0000, v42
	v_pk_mov_b32 v[14:15], v[42:43], v[52:53] op_sel:[1,0]
	v_lshlrev_b32_e32 v17, 16, v52
	v_pk_fma_f32 v[52:53], v[8:9], v[8:9], v[6:7] op_sel_hi:[1,1,0]
	v_lshlrev_b32_e32 v30, 16, v42
	v_lshlrev_b32_e32 v16, 16, v43
	v_pk_mul_f32 v[42:43], v[28:29], v[28:29]
	v_mov_b32_e32 v51, v46
	v_mov_b32_e32 v53, v49
	v_and_b32_e32 v15, 0xffff0000, v15
	v_and_b32_e32 v14, 0xffff0000, v14
	v_pk_fma_f32 v[42:43], v[30:31], v[30:31], v[42:43]
	v_pk_add_f32 v[50:51], v[50:51], v[52:53]
	v_mul_f32_e32 v6, v33, v33
	v_pk_add_f32 v[42:43], v[42:43], v[50:51]
	v_pk_mul_f32 v[50:51], v[14:15], v[14:15]
	v_mov_b32_e32 v52, v54
	v_pk_fma_f32 v[50:51], v[16:17], v[16:17], v[50:51]
	v_mov_b32_e32 v53, v7
	v_pk_add_f32 v[42:43], v[50:51], v[42:43]
	v_pk_fma_f32 v[50:51], v[32:33], v[32:33], v[6:7] op_sel_hi:[1,1,0]
	v_mul_f32_e32 v56, v0, v0
	v_mov_b32_e32 v6, v50
	v_pk_add_f32 v[50:51], v[50:51], v[54:55]
	v_pk_mul_f32 v[52:53], v[6:7], v[52:53]
	v_pk_add_f32 v[34:35], v[34:35], v[44:45] op_sel:[1,0] op_sel_hi:[0,1]
	v_mov_b32_e32 v51, v53
	v_mov_b32_e32 v35, v56
	v_pk_add_f32 v[34:35], v[50:51], v[34:35]
	s_waitcnt vmcnt(0) lgkmcnt(0)
	v_and_b32_e32 v189, 0xffff0000, v5
	v_pk_add_f32 v[34:35], v[34:35], v[42:43]
	global_load_dwordx4 v[42:45], v[98:99], off offset:16
	global_load_dwordx4 v[50:53], v[98:99], off
	v_lshlrev_b32_e32 v174, 16, v3
	v_and_b32_e32 v176, 0xffff0000, v3
	v_add_f32_e32 v3, v34, v35
	ds_bpermute_b32 v6, v215, v3
	v_and_b32_e32 v188, 0xffff0000, v4
	v_lshlrev_b32_e32 v187, 16, v5
	v_lshlrev_b32_e32 v186, 16, v4
	v_pk_mul_f32 v[4:5], v[188:189], v[188:189]
	s_waitcnt lgkmcnt(0)
	v_add_f32_e32 v3, v3, v6
	ds_bpermute_b32 v6, v216, v3
	v_pk_fma_f32 v[190:191], v[186:187], v[186:187], v[4:5]
	v_lshlrev_b32_e32 v184, 16, v2
	v_and_b32_e32 v185, 0xffff0000, v2
	s_waitcnt lgkmcnt(0)
	v_add_f32_e32 v3, v3, v6
	v_fmamk_f32 v3, v3, 0x3c000000, v197
	v_cmp_gt_f32_e32 vcc, s47, v3
	v_mul_f32_e32 v6, 0x4b800000, v3
	s_nop 0
	v_cndmask_b32_e32 v3, v3, v6, vcc
	v_rsq_f32_e32 v3, v3
	s_nop 0
	v_mul_f32_e32 v6, 0x45800000, v3
	v_cndmask_b32_e32 v3, v3, v6, vcc
	v_mul_f32_e32 v6, v3, v41
	v_mul_f32_e32 v34, v3, v39
	v_mul_f32_e32 v35, v3, v37
	v_mul_f32_e32 v24, v3, v24
	v_mul_f32_e32 v20, v3, v20
	v_mul_f32_e32 v0, v3, v0
	s_waitcnt vmcnt(0)
	v_mul_f32_e32 v6, v50, v6
	v_mul_f32_e32 v34, v51, v34
	v_cvt_pk_bf16_f32 v34, v6, v34
	v_mul_f32_e32 v6, v3, v36
	v_mul_f32_e32 v6, v52, v6
	v_mul_f32_e32 v35, v53, v35
	v_cvt_pk_bf16_f32 v35, v6, v35
	v_mul_f32_e32 v6, v3, v40
	v_mul_f32_e32 v36, v3, v38
	v_mul_f32_e32 v6, v42, v6
	v_mul_f32_e32 v36, v43, v36
	v_cvt_pk_bf16_f32 v36, v6, v36
	v_mul_f32_e32 v6, v3, v32
	v_mul_f32_e32 v32, v3, v33
	v_mul_f32_e32 v6, v44, v6
	v_mul_f32_e32 v32, v45, v32
	v_cvt_pk_bf16_f32 v37, v6, v32
	global_load_dwordx4 v[40:43], v[98:99], off offset:144
	global_load_dwordx4 v[50:53], v[98:99], off offset:128
	v_mul_f32_e32 v6, v3, v26
	s_waitcnt vmcnt(1)
	v_mul_f32_e32 v20, v41, v20
	s_waitcnt vmcnt(0)
	v_mul_f32_e32 v6, v50, v6
	v_mul_f32_e32 v24, v51, v24
	v_cvt_pk_bf16_f32 v38, v6, v24
	v_mul_f32_e32 v6, v3, v27
	v_mul_f32_e32 v6, v52, v6
	v_mul_f32_e32 v24, v3, v25
	v_mul_f32_e32 v24, v53, v24
	v_cvt_pk_bf16_f32 v39, v6, v24
	v_mul_f32_e32 v6, v3, v22
	v_mul_f32_e32 v6, v40, v6
	v_cvt_pk_bf16_f32 v40, v6, v20
	v_mul_f32_e32 v20, v3, v21
	v_mul_f32_e32 v6, v3, v23
	v_mul_f32_e32 v20, v43, v20
	v_mul_f32_e32 v6, v42, v6
	v_cvt_pk_bf16_f32 v41, v6, v20
	global_load_dwordx4 v[20:23], v[98:99], off offset:272
	global_load_dwordx4 v[24:27], v[98:99], off offset:256
	v_mul_f32_e32 v6, v3, v18
	v_mul_f32_e32 v18, v3, v19
	s_waitcnt vmcnt(0)
; __device__ __forceinline__ unsigned cvt_pk_bf16(float lo, float hi) { unsigned r; asm volatile("v_cvt_pk_bf16_f32 %0, %1, %2" : "=v"(r) : "v"(lo), "v"(hi)); return r; }
; __device__ __forceinline__ float bflo(unsigned w) { return __uint_as_float(w << 16); }
; __device__ __forceinline__ float bfhi(unsigned w) { return __uint_as_float(w & 0xffff0000u); }
; #define UNPK8(VV_, XX_) float XX_[8] = {bflo((VV_).x), bfhi((VV_).x), bflo((VV_).y), bfhi((VV_).y), bflo((VV_).z), bfhi((VV_).z), bflo((VV_).w), bfhi((VV_).w)}
; __device__ __forceinline__ void kvproj_task(int t, int l, const float* kvnorm, const float* kgain, const bf16_t* P, const bf16_t* WUKV, bf16_t* KB, bf16_t* VT, int fr, int fq) {
;     ...
;     for (int tb = 0; tb < 2; ++tb) { const int row = row0 + tb * 16; float ss = 0.f; u32x4 raw[4];
; #pragma unroll
;         for (int ks = 0; ks < 4; ++ks) { raw[ks] = ld8(P + (size_t)row * INP + ks * 32 + fq * 8); UNPK8(raw[ks], x);
;             ss += (x[0] * x[0] + x[1] * x[1]) + (x[2] * x[2] + x[3] * x[3]) + (x[4] * x[4] + x[5] * x[5]) + (x[6] * x[6] + x[7] * x[7]); }
; #pragma unroll
;         for (int cbr = 0; cbr < 2; ++cbr) { const u32x2 w = ld4(P + (size_t)row * INP + OFF_KROPE + cbr * 16 + fq * 4); kr[tb][cbr] = (f32x4){bflo(w.x), bfhi(w.x), bflo(w.y), bfhi(w.y)}; }
;         ss += __shfl_xor(ss, 16); ss += __shfl_xor(ss, 32);
;         const float rinv = rsqrtf(ss * (1.f / 128.f) + EPS);
; #pragma unroll
;         for (int ks = 0; ks < 4; ++ks) { const float* gp = kvnorm + l * 128 + ks * 32 + fq * 8; const f32x4 g0 = *(const f32x4*)gp, g1 = *(const f32x4*)(gp + 4); UNPK8(raw[ks], x); u32x4 o;
;             o.x = cvt_pk_bf16(x[0] * rinv * g0[0], x[1] * rinv * g0[1]); o.y = cvt_pk_bf16(x[2] * rinv * g0[2], x[3] * rinv * g0[3]);
;             o.z = cvt_pk_bf16(x[4] * rinv * g1[0], x[5] * rinv * g1[1]); o.w = cvt_pk_bf16(x[6] * rinv * g1[2], x[7] * rinv * g1[3]);
;             bfr[tb][ks] = asfrag(o); }
;         skr[tb] = (kr[tb][0][0] * kr[tb][0][0] + kr[tb][0][1] * kr[tb][0][1]) + (kr[tb][0][2] * kr[tb][0][2] + kr[tb][0][3] * kr[tb][0][3]) + (kr[tb][1][0] * kr[tb][1][0] + kr[tb][1][1] * kr[tb][1][1]) + (kr[tb][1][2] * kr[tb][1][2] + kr[tb][1][3] * kr[tb][1][3]); }
	v_mul_f32_e32 v6, v24, v6
	v_mul_f32_e32 v18, v25, v18
	v_cvt_pk_bf16_f32 v42, v6, v18
	v_mul_f32_e32 v6, v3, v8
	v_mul_f32_e32 v8, v3, v9
	v_mul_f32_e32 v6, v26, v6
	v_mul_f32_e32 v8, v27, v8
	v_cvt_pk_bf16_f32 v43, v6, v8
	v_mul_f32_e32 v6, v3, v30
	v_mul_f32_e32 v8, v3, v28
	v_mul_f32_e32 v6, v20, v6
	v_mul_f32_e32 v8, v21, v8
	v_cvt_pk_bf16_f32 v44, v6, v8
	v_mul_f32_e32 v6, v3, v16
	v_mul_f32_e32 v8, v3, v14
	v_mul_f32_e32 v6, v22, v6
	v_mul_f32_e32 v8, v23, v8
	v_cvt_pk_bf16_f32 v45, v6, v8
	global_load_dwordx4 v[18:21], v[98:99], off offset:400
	global_load_dwordx4 v[22:25], v[98:99], off offset:384
	v_mul_f32_e32 v6, v3, v31
	v_mul_f32_e32 v8, v3, v29
	s_waitcnt vmcnt(1)
	v_mul_f32_e32 v0, v0, v21
	s_waitcnt vmcnt(0)
	v_mul_f32_e32 v6, v6, v22
	v_mul_f32_e32 v8, v8, v23
	v_cvt_pk_bf16_f32 v46, v6, v8
	v_mul_f32_e32 v6, v3, v48
	v_mul_f32_e32 v6, v6, v24
	v_mul_f32_e32 v8, v3, v47
	v_mul_f32_e32 v8, v8, v25
	v_cvt_pk_bf16_f32 v47, v6, v8
	v_mul_f32_e32 v6, v3, v17
	v_mul_f32_e32 v6, v6, v18
	v_mul_f32_e32 v8, v3, v15
	v_mul_f32_e32 v8, v8, v19
	v_cvt_pk_bf16_f32 v48, v6, v8
	v_mul_f32_e32 v6, v3, v7
	v_mul_f32_e32 v6, v6, v20
	v_mad_i64_i32 v[14:15], s[6:7], v173, s84, v[94:95]
	v_cvt_pk_bf16_f32 v49, v6, v0
	global_load_dwordx4 v[2:5], v[14:15], off
	global_load_dwordx4 v[6:9], v[14:15], off offset:64
	s_waitcnt vmcnt(0) lgkmcnt(0)
	v_and_b32_e32 v33, 0xffff0000, v3
	v_and_b32_e32 v27, 0xffff0000, v7
	v_and_b32_e32 v26, 0xffff0000, v6
	v_lshlrev_b32_e32 v29, 16, v7
	v_lshlrev_b32_e32 v28, 16, v6
	v_pk_mul_f32 v[6:7], v[26:27], v[26:27]
	v_and_b32_e32 v23, 0xffff0000, v9
	v_and_b32_e32 v22, 0xffff0000, v8
	v_pk_fma_f32 v[6:7], v[28:29], v[28:29], v[6:7]
	v_lshlrev_b32_e32 v25, 16, v9
	v_lshlrev_b32_e32 v24, 16, v8
	v_pk_mul_f32 v[8:9], v[22:23], v[22:23]
	v_pk_add_f32 v[6:7], v[6:7], v[6:7] op_sel:[0,1] op_sel_hi:[1,0]
	v_pk_fma_f32 v[50:51], v[24:25], v[24:25], v[8:9]
	v_and_b32_e32 v57, 0xffff0000, v2
	v_pk_add_f32 v[52:53], v[50:51], v[6:7]
	global_load_dwordx4 v[6:9], v[14:15], off offset:128
	v_and_b32_e32 v56, 0xffff0000, v4
	global_load_dwordx4 v[14:17], v[14:15], off offset:192
	v_lshlrev_b32_e32 v32, 16, v3
	v_mul_f32_e32 v0, v33, v33
	v_lshlrev_b32_e32 v59, 16, v2
	v_lshlrev_b32_e32 v58, 16, v4
	v_pk_fma_f32 v[54:55], v[32:33], v[32:33], v[0:1] op_sel_hi:[1,1,0]
	v_lshlrev_b32_e32 v30, 16, v5
	v_and_b32_e32 v31, 0xffff0000, v5
	s_waitcnt vmcnt(0) lgkmcnt(0)
	v_lshlrev_b32_e32 v20, 16, v6
	v_and_b32_e32 v21, 0xffff0000, v6
	v_lshlrev_b32_e32 v18, 16, v7
	v_and_b32_e32 v19, 0xffff0000, v7
	v_mad_i64_i32 v[6:7], s[6:7], v173, s84, v[168:169]
	global_load_dwordx2 v[68:69], v[6:7], off offset:256
	global_load_dwordx2 v[66:67], v[6:7], off offset:288
	v_pk_mul_f32 v[6:7], v[56:57], v[56:57]
	v_and_b32_e32 v0, 0xffff0000, v17
	v_pk_fma_f32 v[6:7], v[58:59], v[58:59], v[6:7]
	v_lshlrev_b32_e32 v73, 16, v15
	v_pk_add_f32 v[54:55], v[6:7], v[54:55] op_sel:[1,0] op_sel_hi:[0,1]
	v_mul_f32_e32 v3, v0, v0
	v_pk_add_f32 v[6:7], v[6:7], v[54:55]
	v_pk_mov_b32 v[54:55], v[8:9], v[16:17] op_sel:[1,0]
	v_mul_f32_e32 v2, v21, v21
	v_and_b32_e32 v72, 0xffff0000, v15
	v_lshlrev_b32_e32 v15, 16, v17
	v_mul_f32_e32 v60, v73, v73
	v_lshlrev_b32_e32 v65, 16, v16
	v_and_b32_e32 v17, 0xffff0000, v55
	v_and_b32_e32 v16, 0xffff0000, v54
	v_pk_fma_f32 v[54:55], v[20:21], v[20:21], v[2:3] op_sel_hi:[1,1,0]
	v_mul_f32_e32 v2, v19, v19
	v_mul_f32_e32 v5, v72, v72
	v_and_b32_e32 v63, 0xffff0000, v14
	v_and_b32_e32 v62, 0xffff0000, v8
	v_mov_b32_e32 v55, v60
	v_pk_fma_f32 v[60:61], v[18:19], v[18:19], v[2:3] op_sel_hi:[1,1,0]
	v_lshlrev_b32_e32 v71, 16, v14
	v_lshlrev_b32_e32 v70, 16, v8
	v_lshlrev_b32_e32 v64, 16, v9
	v_pk_mul_f32 v[8:9], v[62:63], v[62:63]
	v_mov_b32_e32 v61, v5
	v_pk_fma_f32 v[8:9], v[70:71], v[70:71], v[8:9]
	v_pk_add_f32 v[4:5], v[54:55], v[60:61]
	v_mul_f32_e32 v2, v31, v31
	v_pk_add_f32 v[4:5], v[8:9], v[4:5]
	v_pk_mul_f32 v[8:9], v[16:17], v[16:17]
	v_mov_b32_e32 v54, v6
	v_pk_fma_f32 v[8:9], v[64:65], v[64:65], v[8:9]
	v_mov_b32_e32 v55, v15
	v_pk_add_f32 v[4:5], v[8:9], v[4:5]
	v_pk_fma_f32 v[8:9], v[30:31], v[30:31], v[2:3] op_sel_hi:[1,1,0]
	s_waitcnt vmcnt(0) lgkmcnt(0)
	v_and_b32_e32 v183, 0xffff0000, v69
	v_mov_b32_e32 v14, v8
	v_pk_add_f32 v[6:7], v[8:9], v[6:7]
	v_pk_mul_f32 v[8:9], v[14:15], v[54:55]
	v_and_b32_e32 v182, 0xffff0000, v68
	v_mov_b32_e32 v7, v9
	v_pk_add_f32 v[8:9], v[50:51], v[52:53] op_sel:[1,0] op_sel_hi:[0,1]
	v_mov_b32_e32 v9, v3
	v_pk_add_f32 v[2:3], v[6:7], v[8:9]
	v_lshlrev_b32_e32 v181, 16, v69
	v_pk_add_f32 v[2:3], v[2:3], v[4:5]
	v_lshlrev_b32_e32 v180, 16, v68
	v_add_f32_e32 v2, v2, v3
	ds_bpermute_b32 v3, v215, v2
	v_lshlrev_b32_e32 v170, 16, v67
	v_and_b32_e32 v172, 0xffff0000, v67
	v_lshlrev_b32_e32 v178, 16, v66
	v_and_b32_e32 v179, 0xffff0000, v66
	s_waitcnt lgkmcnt(0)
	v_add_f32_e32 v2, v2, v3
	ds_bpermute_b32 v3, v216, v2
	s_waitcnt lgkmcnt(0)
	v_add_f32_e32 v2, v2, v3
	v_fmamk_f32 v2, v2, 0x3c000000, v197
	v_cmp_gt_f32_e32 vcc, s47, v2
	v_mul_f32_e32 v3, 0x4b800000, v2
	s_nop 0
	v_cndmask_b32_e32 v2, v2, v3, vcc
	v_rsq_f32_e32 v2, v2
	s_nop 0
	v_mul_f32_e32 v3, 0x45800000, v2
	v_cndmask_b32_e32 v14, v2, v3, vcc
	global_load_dwordx4 v[2:5], v[98:99], off offset:16
	global_load_dwordx4 v[6:9], v[98:99], off
	v_mul_f32_e32 v50, v14, v59
	v_mul_f32_e32 v28, v14, v28
	v_mul_f32_e32 v26, v14, v26
	v_mul_f32_e32 v20, v14, v20
	v_mul_f32_e32 v0, v14, v0
	v_cmp_lt_i32_e32 vcc, s49, v171
	s_waitcnt vmcnt(0)
; __device__ __forceinline__ unsigned cvt_pk_bf16(float lo, float hi) { unsigned r; asm volatile("v_cvt_pk_bf16_f32 %0, %1, %2" : "=v"(r) : "v"(lo), "v"(hi)); return r; }
; #define MFMA16(a, b, c) __builtin_amdgcn_mfma_f32_16x16x32_bf16((a), (b), (c), 0, 0, 0)
; #define UNPK8(VV_, XX_) float XX_[8] = {bflo((VV_).x), bfhi((VV_).x), bflo((VV_).y), bfhi((VV_).y), bflo((VV_).z), bfhi((VV_).z), bflo((VV_).w), bfhi((VV_).w)}
; __device__ __forceinline__ void kvproj_task(int t, int l, const float* kvnorm, const float* kgain, const bf16_t* P, const bf16_t* WUKV, bf16_t* KB, bf16_t* VT, int fr, int fq) {
;     ...
;         for (int ks = 0; ks < 4; ++ks) { const float* gp = kvnorm + l * 128 + ks * 32 + fq * 8; const f32x4 g0 = *(const f32x4*)gp, g1 = *(const f32x4*)(gp + 4); UNPK8(raw[ks], x); u32x4 o;
;             o.x = cvt_pk_bf16(x[0] * rinv * g0[0], x[1] * rinv * g0[1]); o.y = cvt_pk_bf16(x[2] * rinv * g0[2], x[3] * rinv * g0[3]);
;             o.z = cvt_pk_bf16(x[4] * rinv * g1[0], x[5] * rinv * g1[1]); o.w = cvt_pk_bf16(x[6] * rinv * g1[2], x[7] * rinv * g1[3]);
;             bfr[tb][ks] = asfrag(o); }
;         skr[tb] = (kr[tb][0][0] * kr[tb][0][0] + kr[tb][0][1] * kr[tb][0][1]) + (kr[tb][0][2] * kr[tb][0][2] + kr[tb][0][3] * kr[tb][0][3]) + (kr[tb][1][0] * kr[tb][1][0] + kr[tb][1][1] * kr[tb][1][1]) + (kr[tb][1][2] * kr[tb][1][2] + kr[tb][1][3] * kr[tb][1][3]); }
;     const bf16_t* wk0 = WUKV + ((size_t)l * 512 + h * 128 + fr) * 128 + fq * 8;
;     bf16x8 wf[2][4];
; #pragma unroll
;     for (int ks = 0; ks < 4; ++ks) wf[0][ks] = asfrag(ld8(wk0 + ks * 32));
;     f32x4 acc[2][8];
; #pragma unroll
;     for (int cb = 0; cb < 8; ++cb) { acc[0][cb] = (f32x4){0.f, 0.f, 0.f, 0.f}; acc[1][cb] = acc[0][cb];
;         const int nrow = cb < 7 ? (cb + 1) * 16 : 0;
; #pragma unroll
;         for (int ks = 0; ks < 4; ++ks) wf[(cb + 1) & 1][ks] = asfrag(ld8(wk0 + (size_t)nrow * 128 + ks * 32));
; #pragma unroll
;         for (int ks = 0; ks < 4; ++ks) { acc[0][cb] = MFMA16(wf[cb & 1][ks], bfr[0][ks], acc[0][cb]); acc[1][cb] = MFMA16(wf[cb & 1][ks], bfr[1][ks], acc[1][cb]); } }
	v_mul_f32_e32 v6, v6, v50
	v_mul_f32_e32 v50, v14, v57
	v_mul_f32_e32 v7, v7, v50
	v_cvt_pk_bf16_f32 v50, v6, v7
	v_mul_f32_e32 v6, v14, v32
	v_mul_f32_e32 v6, v8, v6
	v_mul_f32_e32 v7, v14, v33
	v_mul_f32_e32 v7, v9, v7
	v_cvt_pk_bf16_f32 v51, v6, v7
	v_mul_f32_e32 v6, v14, v58
	v_mul_f32_e32 v2, v2, v6
	v_mul_f32_e32 v6, v14, v56
	v_mul_f32_e32 v3, v3, v6
	v_cvt_pk_bf16_f32 v52, v2, v3
	v_mul_f32_e32 v2, v14, v30
	v_mul_f32_e32 v3, v14, v31
	v_mul_f32_e32 v2, v4, v2
	v_mul_f32_e32 v3, v5, v3
	v_cvt_pk_bf16_f32 v53, v2, v3
	global_load_dwordx4 v[2:5], v[98:99], off offset:144
	global_load_dwordx4 v[6:9], v[98:99], off offset:128
	s_waitcnt vmcnt(0)
	v_mul_f32_e32 v6, v6, v28
	v_mul_f32_e32 v7, v7, v26
	v_cvt_pk_bf16_f32 v54, v6, v7
	v_mul_f32_e32 v6, v14, v29
	v_mul_f32_e32 v6, v8, v6
	v_mul_f32_e32 v7, v14, v27
	v_mul_f32_e32 v7, v9, v7
	v_cvt_pk_bf16_f32 v55, v6, v7
	v_mul_f32_e32 v6, v14, v24
	v_mul_f32_e32 v2, v2, v6
	v_mul_f32_e32 v6, v14, v22
	v_mul_f32_e32 v3, v3, v6
	v_cvt_pk_bf16_f32 v56, v2, v3
	v_mul_f32_e32 v2, v14, v25
	v_mul_f32_e32 v3, v14, v23
	v_mul_f32_e32 v2, v4, v2
	v_mul_f32_e32 v3, v5, v3
	v_cvt_pk_bf16_f32 v57, v2, v3
	global_load_dwordx4 v[2:5], v[98:99], off offset:272
	global_load_dwordx4 v[6:9], v[98:99], off offset:256
	s_waitcnt vmcnt(0)
	v_mul_f32_e32 v6, v6, v20
	v_mul_f32_e32 v20, v14, v21
	v_mul_f32_e32 v7, v7, v20
	v_cvt_pk_bf16_f32 v58, v6, v7
	v_mul_f32_e32 v6, v14, v18
	v_mul_f32_e32 v6, v8, v6
	v_mul_f32_e32 v7, v14, v19
	v_mul_f32_e32 v7, v9, v7
	v_cvt_pk_bf16_f32 v59, v6, v7
	v_mul_f32_e32 v6, v14, v70
	v_mul_f32_e32 v2, v2, v6
	v_mul_f32_e32 v6, v14, v62
	v_mul_f32_e32 v3, v3, v6
	v_cvt_pk_bf16_f32 v60, v2, v3
	v_mul_f32_e32 v2, v14, v64
	v_mul_f32_e32 v3, v14, v16
	v_mul_f32_e32 v2, v4, v2
	v_mul_f32_e32 v3, v5, v3
	v_cvt_pk_bf16_f32 v61, v2, v3
	global_load_dwordx4 v[2:5], v[98:99], off offset:400
	global_load_dwordx4 v[6:9], v[98:99], off offset:384
	v_mul_f32_e32 v16, v14, v71
	s_waitcnt vmcnt(1)
	v_mul_f32_e32 v0, v0, v5
	s_waitcnt vmcnt(0)
	v_mul_f32_e32 v6, v16, v6
	v_mul_f32_e32 v16, v14, v63
	v_mul_f32_e32 v7, v16, v7
	v_cvt_pk_bf16_f32 v62, v6, v7
	v_mul_f32_e32 v6, v14, v73
	v_mul_f32_e32 v6, v6, v8
	v_mul_f32_e32 v7, v14, v72
	v_mul_f32_e32 v7, v7, v9
	v_cvt_pk_bf16_f32 v63, v6, v7
	v_mul_f32_e32 v6, v14, v65
	v_mul_f32_e32 v2, v6, v2
	v_mul_f32_e32 v6, v14, v17
	v_mul_f32_e32 v3, v6, v3
	v_cvt_pk_bf16_f32 v64, v2, v3
	v_mul_f32_e32 v2, v14, v15
	v_mul_f32_e32 v2, v2, v4
	v_cvt_pk_bf16_f32 v65, v2, v0
	v_pk_mul_f32 v[2:3], v[182:183], v[182:183]
	v_add_u32_e32 v0, 0xffffc000, v171
	v_pk_fma_f32 v[192:193], v[180:181], v[180:181], v[2:3]
	global_load_dwordx4 v[2:5], v[104:105], off
	global_load_dwordx4 v[6:9], v[104:105], off offset:64
	global_load_dwordx4 v[14:17], v[104:105], off offset:128
	global_load_dwordx4 v[18:21], v[104:105], off offset:192
	global_load_dwordx4 v[22:25], v[106:107], off
	global_load_dwordx4 v[26:29], v[108:109], off
	global_load_dwordx4 v[30:33], v[110:111], off
	global_load_dwordx4 v[74:77], v[112:113], off
	s_waitcnt vmcnt(0) lgkmcnt(0)
	v_mfma_f32_16x16x32_bf16 v[66:69], v[2:5], v[34:37], 0
	v_mfma_f32_16x16x32_bf16 v[2:5], v[2:5], v[50:53], 0
	v_mfma_f32_16x16x32_bf16 v[66:69], v[6:9], v[38:41], v[66:69]
	v_mfma_f32_16x16x32_bf16 v[2:5], v[6:9], v[54:57], v[2:5]
	v_mfma_f32_16x16x32_bf16 v[6:9], v[14:17], v[42:45], v[66:69]
	v_mfma_f32_16x16x32_bf16 v[2:5], v[14:17], v[58:61], v[2:5]
	v_mfma_f32_16x16x32_bf16 v[66:69], v[18:21], v[46:49], v[6:9]
	v_mfma_f32_16x16x32_bf16 v[6:9], v[22:25], v[34:37], 0
	v_mfma_f32_16x16x32_bf16 v[22:25], v[22:25], v[50:53], 0
	s_nop 5
	v_mov_b32_e32 v177, v67
	v_mov_b32_e32 v175, v66
	v_mfma_f32_16x16x32_bf16 v[2:5], v[18:21], v[62:65], v[2:5]
	global_load_dwordx4 v[14:17], v[114:115], off
	global_load_dwordx4 v[18:21], v[116:117], off
	global_load_dwordx4 v[78:81], v[118:119], off
	global_load_dwordx4 v[82:85], v[120:121], off
	v_mfma_f32_16x16x32_bf16 v[6:9], v[26:29], v[38:41], v[6:9]
	v_mfma_f32_16x16x32_bf16 v[22:25], v[26:29], v[54:57], v[22:25]
	v_mfma_f32_16x16x32_bf16 v[6:9], v[30:33], v[42:45], v[6:9]
	v_mfma_f32_16x16x32_bf16 v[22:25], v[30:33], v[58:61], v[22:25]
	v_mfma_f32_16x16x32_bf16 v[70:73], v[74:77], v[46:49], v[6:9]
	v_mfma_f32_16x16x32_bf16 v[6:9], v[74:77], v[62:65], v[22:25]
	s_nop 5
	global_load_dwordx4 v[22:25], v[122:123], off
	global_load_dwordx4 v[26:29], v[124:125], off
	global_load_dwordx4 v[30:33], v[126:127], off
	global_load_dwordx4 v[74:77], v[128:129], off
	s_waitcnt vmcnt(0) lgkmcnt(0)
	v_mfma_f32_16x16x32_bf16 v[86:89], v[14:17], v[34:37], 0
	v_mfma_f32_16x16x32_bf16 v[14:17], v[14:17], v[50:53], 0
	v_mfma_f32_16x16x32_bf16 v[86:89], v[18:21], v[38:41], v[86:89]
	v_mfma_f32_16x16x32_bf16 v[14:17], v[18:21], v[54:57], v[14:17]
	v_mfma_f32_16x16x32_bf16 v[18:21], v[78:81], v[42:45], v[86:89]
	v_mfma_f32_16x16x32_bf16 v[86:89], v[22:25], v[34:37], 0
	v_mfma_f32_16x16x32_bf16 v[22:25], v[22:25], v[50:53], 0
	v_mfma_f32_16x16x32_bf16 v[14:17], v[78:81], v[58:61], v[14:17]
	v_mfma_f32_16x16x32_bf16 v[86:89], v[26:29], v[38:41], v[86:89]
	v_mfma_f32_16x16x32_bf16 v[22:25], v[26:29], v[54:57], v[22:25]
	v_mfma_f32_16x16x32_bf16 v[78:81], v[82:85], v[46:49], v[18:21]
	v_mfma_f32_16x16x32_bf16 v[18:21], v[82:85], v[62:65], v[14:17]
	s_nop 3
	global_load_dwordx4 v[14:17], v[130:131], off
	global_load_dwordx4 v[82:85], v[132:133], off
	global_load_dwordx4 v[90:93], v[134:135], off
	global_load_dwordx4 v[222:225], v[136:137], off
	v_mfma_f32_16x16x32_bf16 v[26:29], v[30:33], v[42:45], v[86:89]
	v_mfma_f32_16x16x32_bf16 v[22:25], v[30:33], v[58:61], v[22:25]
	v_mfma_f32_16x16x32_bf16 v[86:89], v[74:77], v[46:49], v[26:29]
	v_mfma_f32_16x16x32_bf16 v[26:29], v[74:77], v[62:65], v[22:25]
	s_nop 5
	global_load_dwordx4 v[22:25], v[138:139], off
	global_load_dwordx4 v[30:33], v[140:141], off
	global_load_dwordx4 v[226:229], v[142:143], off
	global_load_dwordx4 v[230:233], v[144:145], off
	s_waitcnt vmcnt(0) lgkmcnt(0)
; __device__ __forceinline__ unsigned cvt_pk_bf16(float lo, float hi) { unsigned r; asm volatile("v_cvt_pk_bf16_f32 %0, %1, %2" : "=v"(r) : "v"(lo), "v"(hi)); return r; }
; #define MFMA16(a, b, c) __builtin_amdgcn_mfma_f32_16x16x32_bf16((a), (b), (c), 0, 0, 0)
; __device__ __forceinline__ void kvproj_task(int t, int l, const float* kvnorm, const float* kgain, const bf16_t* P, const bf16_t* WUKV, bf16_t* KB, bf16_t* VT, int fr, int fq) {
;     ...
;     for (int cb = 0; cb < 8; ++cb) { acc[0][cb] = (f32x4){0.f, 0.f, 0.f, 0.f}; acc[1][cb] = acc[0][cb];
;         const int nrow = cb < 7 ? (cb + 1) * 16 : 0;
; #pragma unroll
;         for (int ks = 0; ks < 4; ++ks) wf[(cb + 1) & 1][ks] = asfrag(ld8(wk0 + (size_t)nrow * 128 + ks * 32));
; #pragma unroll
;         for (int ks = 0; ks < 4; ++ks) { acc[0][cb] = MFMA16(wf[cb & 1][ks], bfr[0][ks], acc[0][cb]); acc[1][cb] = MFMA16(wf[cb & 1][ks], bfr[1][ks], acc[1][cb]); } }
; #pragma unroll
;     for (int tb = 0; tb < 2; ++tb) { const int row = row0 + tb * 16, rr = isc ? row - ML : row;
;         const int b = isc ? rr >> 8 : rr >> 11, tpos = isc ? rr & 255 : rr & 2047, key = isc ? tpos : 256 + tpos;
;         float s2 = skr[tb];
; #pragma unroll
;         for (int cb = 0; cb < 4; ++cb) s2 += (acc[tb][cb][0] * acc[tb][cb][0] + acc[tb][cb][1] * acc[tb][cb][1]) + (acc[tb][cb][2] * acc[tb][cb][2] + acc[tb][cb][3] * acc[tb][cb][3]);
;         s2 += __shfl_xor(s2, 16); s2 += __shfl_xor(s2, 32);
;         const float rh = rsqrtf(s2 * (1.f / 96.f) + EPS);
;         bf16_t* kdst = KB + ((size_t)(b * 4 + h) * NKEY + key) * 96;
; #pragma unroll
;         for (int cb = 0; cb < 6; ++cb) { const f32x4 kg = *(const f32x4*)(kgain + l * 96 + cb * 16 + fq * 4); f32x4 v = (cb < 4 ? acc[tb][cb < 4 ? cb : 0] : kr[tb][cb >= 4 ? cb - 4 : 0]) * rh * kg;
;             if (cb >= 4) { const f32x4 rv = rope16(v, fq, (float)(cb == 4 ? (tpos >> 6) : (tpos & 63))); if (!isc) v = rv; }
;             u32x2 w; w.x = cvt_pk_bf16(v[0], v[1]); w.y = cvt_pk_bf16(v[2], v[3]);
;             *(u32x2*)(kdst + cb * 16 + fq * 4) = w; }
	v_mfma_f32_16x16x32_bf16 v[74:77], v[14:17], v[34:37], 0
	v_mfma_f32_16x16x32_bf16 v[14:17], v[14:17], v[50:53], 0
	v_mfma_f32_16x16x32_bf16 v[74:77], v[82:85], v[38:41], v[74:77]
	v_mfma_f32_16x16x32_bf16 v[14:17], v[82:85], v[54:57], v[14:17]
	v_mfma_f32_16x16x32_bf16 v[82:85], v[22:25], v[34:37], 0
	v_mfma_f32_16x16x32_bf16 v[22:25], v[22:25], v[50:53], 0
	v_mfma_f32_16x16x32_bf16 v[82:85], v[30:33], v[38:41], v[82:85]
	v_mfma_f32_16x16x32_bf16 v[22:25], v[30:33], v[54:57], v[22:25]
	v_mfma_f32_16x16x32_bf16 v[74:77], v[90:93], v[42:45], v[74:77]
	v_mfma_f32_16x16x32_bf16 v[14:17], v[90:93], v[58:61], v[14:17]
	v_mfma_f32_16x16x32_bf16 v[30:33], v[226:229], v[42:45], v[82:85]
	v_mfma_f32_16x16x32_bf16 v[22:25], v[226:229], v[58:61], v[22:25]
	v_mfma_f32_16x16x32_bf16 v[74:77], v[222:225], v[46:49], v[74:77]
	v_mfma_f32_16x16x32_bf16 v[14:17], v[222:225], v[62:65], v[14:17]
	global_load_dwordx4 v[90:93], v[146:147], off
	global_load_dwordx4 v[222:225], v[148:149], off
	global_load_dwordx4 v[234:237], v[156:157], off
	global_load_dwordx4 v[238:241], v[158:159], off
	v_mfma_f32_16x16x32_bf16 v[82:85], v[230:233], v[46:49], v[30:33]
	v_mfma_f32_16x16x32_bf16 v[22:25], v[230:233], v[62:65], v[22:25]
	global_load_dwordx4 v[226:229], v[160:161], off
	global_load_dwordx4 v[230:233], v[162:163], off
	global_load_dwordx4 v[242:245], v[164:165], off
	global_load_dwordx4 v[246:249], v[166:167], off
	s_waitcnt vmcnt(0) lgkmcnt(0)
	v_mfma_f32_16x16x32_bf16 v[30:33], v[90:93], v[34:37], 0
	v_mfma_f32_16x16x32_bf16 v[34:37], v[226:229], v[34:37], 0
	v_mfma_f32_16x16x32_bf16 v[90:93], v[90:93], v[50:53], 0
	v_mfma_f32_16x16x32_bf16 v[50:53], v[226:229], v[50:53], 0
	v_mfma_f32_16x16x32_bf16 v[30:33], v[222:225], v[38:41], v[30:33]
	v_mfma_f32_16x16x32_bf16 v[34:37], v[230:233], v[38:41], v[34:37]
	v_mfma_f32_16x16x32_bf16 v[38:41], v[230:233], v[54:57], v[50:53]
	v_mfma_f32_16x16x32_bf16 v[90:93], v[222:225], v[54:57], v[90:93]
	v_cndmask_b32_e32 v54, v171, v0, vcc
	v_mul_f32_e32 v0, v68, v68
	s_nop 1
	v_mul_f32_e32 v50, v69, v69
	v_mfma_f32_16x16x32_bf16 v[30:33], v[234:237], v[42:45], v[30:33]
	v_mfma_f32_16x16x32_bf16 v[34:37], v[242:245], v[42:45], v[34:37]
	v_mfma_f32_16x16x32_bf16 v[42:45], v[242:245], v[58:61], v[38:41]
	v_mfma_f32_16x16x32_bf16 v[222:225], v[234:237], v[58:61], v[90:93]
	v_mfma_f32_16x16x32_bf16 v[90:93], v[238:241], v[46:49], v[30:33]
	v_mfma_f32_16x16x32_bf16 v[38:41], v[246:249], v[46:49], v[34:37]
	v_add_f32_e64 v46, v190, v191
	v_add_f32_e64 v47, v191, v190
	v_mov_b32_e32 v47, v0
	v_mul_f32_e32 v0, v185, v185
	v_pk_fma_f32 v[48:49], v[184:185], v[184:185], v[0:1] op_sel_hi:[1,1,0]
	v_mfma_f32_16x16x32_bf16 v[34:37], v[246:249], v[62:65], v[42:45]
	v_mov_b32_e32 v49, v50
	v_pk_add_f32 v[46:47], v[46:47], v[48:49]
	v_pk_mul_f32 v[48:49], v[70:71], v[70:71]
	v_pk_mul_f32 v[44:45], v[176:177], v[176:177]
	v_mul_f32_e32 v0, v86, v86
	v_pk_fma_f32 v[44:45], v[174:175], v[174:175], v[44:45]
	v_cndmask_b32_e32 v43, v200, v201, vcc
	v_pk_add_f32 v[44:45], v[44:45], v[46:47]
	v_pk_mul_f32 v[46:47], v[72:73], v[72:73]
	v_pk_add_f32 v[44:45], v[44:45], v[44:45] op_sel:[0,1] op_sel_hi:[1,0]
	v_pk_mov_b32 v[50:51], v[48:49], v[46:47] op_sel:[1,0]
	v_mov_b32_e32 v49, v47
	v_pk_add_f32 v[46:47], v[50:51], v[48:49]
	v_mul_f32_e32 v48, v87, v87
	v_pk_add_f32 v[46:47], v[46:47], v[46:47] op_sel:[0,1] op_sel_hi:[1,0]
	v_mov_b32_e32 v45, v0
	v_mov_b32_e32 v47, v48
	v_mul_f32_e32 v0, v79, v79
	v_mul_f32_e32 v49, v88, v88
	v_pk_add_f32 v[44:45], v[44:45], v[46:47]
	v_pk_fma_f32 v[46:47], v[78:79], v[78:79], v[0:1] op_sel_hi:[1,1,0]
	v_mul_f32_e32 v0, v81, v81
	v_mul_f32_e32 v50, v89, v89
	v_mov_b32_e32 v47, v49
	v_pk_fma_f32 v[48:49], v[80:81], v[80:81], v[0:1] op_sel_hi:[1,1,0]
	v_cndmask_b32_e64 v42, 11, 8, vcc
	v_mov_b32_e32 v49, v50
	v_pk_add_f32 v[46:47], v[46:47], v[48:49]
	v_and_b32_e32 v55, v54, v43
	v_pk_add_f32 v[44:45], v[44:45], v[46:47]
	v_add_u32_e32 v52, 0x100, v55
	v_add_f32_e32 v44, v44, v45
	ds_bpermute_b32 v46, v215, v44
	v_ashrrev_i32_e32 v45, v42, v54
	v_cndmask_b32_e32 v0, v52, v55, vcc
	v_lshl_or_b32 v50, v45, 2, s22
	v_lshrrev_b32_e32 v49, 6, v55
	s_waitcnt lgkmcnt(0)
	v_add_f32_e32 v44, v44, v46
	ds_bpermute_b32 v46, v216, v44
	v_mfma_f32_16x16x32_bf16 v[30:33], v[238:241], v[62:65], v[222:225]
	v_and_b32_e32 v64, 47, v54
	v_mov_b32_e32 v175, v176
	v_ashrrev_i32_e32 v51, 31, v50
	s_waitcnt lgkmcnt(0)
	v_add_f32_e32 v44, v44, v46
	v_fmamk_f32 v44, v44, 0x3c2aaaab, v197
	v_cmp_gt_f32_e64 s[38:39], s47, v44
	v_mul_f32_e32 v46, 0x4b800000, v44
	s_nop 0
	v_cndmask_b32_e64 v44, v44, v46, s[38:39]
	v_rsq_f32_e32 v44, v44
	s_nop 0
	v_mul_f32_e32 v46, 0x45800000, v44
	v_cndmask_b32_e64 v48, v44, v46, s[38:39]
	v_mad_i64_i32 v[44:45], s[6:7], v50, s9, v[0:1]
	v_mad_u64_u32 v[52:53], s[6:7], v44, s14, v[102:103]
	v_mad_i32_i24 v53, v45, s14, v53
	global_load_dwordx4 v[44:47], v[100:101], off
	v_pk_mul_f32 v[56:57], v[66:67], v[48:49] op_sel_hi:[1,0]
	v_pk_mul_f32 v[54:55], v[68:69], v[48:49] op_sel_hi:[1,0]
	v_lshlrev_b32_e32 v0, 1, v0
	s_waitcnt vmcnt(0)
	v_pk_mul_f32 v[44:45], v[44:45], v[56:57]
	v_pk_mul_f32 v[46:47], v[46:47], v[54:55]
	v_cvt_pk_bf16_f32 v44, v44, v45
	v_pk_mul_f32 v[56:57], v[70:71], v[48:49] op_sel_hi:[1,0]
	v_cvt_pk_bf16_f32 v45, v46, v47
	global_store_dwordx2 v[52:53], v[44:45], off
	global_load_dwordx4 v[44:47], v[100:101], off offset:64
	v_pk_mul_f32 v[54:55], v[72:73], v[48:49] op_sel_hi:[1,0]
	s_waitcnt vmcnt(0)
; __device__ __forceinline__ unsigned cvt_pk_bf16(float lo, float hi) { unsigned r; asm volatile("v_cvt_pk_bf16_f32 %0, %1, %2" : "=v"(r) : "v"(lo), "v"(hi)); return r; }
; __device__ __forceinline__ bf16_t tobf(float f) { return (bf16_t)(cvt_pk_bf16(f, 0.f) & 0xffffu); }
; __device__ __forceinline__ f32x4 rope16(f32x4 v, int fq, float pos) {
;     f32x4 pr; pr[0] = __shfl_xor(v[0], 32); pr[1] = __shfl_xor(v[1], 32); pr[2] = __shfl_xor(v[2], 32); pr[3] = __shfl_xor(v[3], 32);
;     f32x4 o;
; #pragma unroll
;     for (int q = 0; q < 4; ++q) { const int f = (fq * 4 + q) & 7; const float inv = __builtin_amdgcn_exp2f(-(float)f * 1.6609640474f); float sn, cs; __sincosf(pos * inv, &sn, &cs);
;         o[q] = fq < 2 ? v[q] * cs - pr[q] * sn : pr[q] * sn + v[q] * cs; }
;     return o;
; __device__ __forceinline__ void kvproj_task(int t, int l, const float* kvnorm, const float* kgain, const bf16_t* P, const bf16_t* WUKV, bf16_t* KB, bf16_t* VT, int fr, int fq) {
;     ...
;         for (int cb = 0; cb < 6; ++cb) { const f32x4 kg = *(const f32x4*)(kgain + l * 96 + cb * 16 + fq * 4); f32x4 v = (cb < 4 ? acc[tb][cb < 4 ? cb : 0] : kr[tb][cb >= 4 ? cb - 4 : 0]) * rh * kg;
;             if (cb >= 4) { const f32x4 rv = rope16(v, fq, (float)(cb == 4 ? (tpos >> 6) : (tpos & 63))); if (!isc) v = rv; }
;             u32x2 w; w.x = cvt_pk_bf16(v[0], v[1]); w.y = cvt_pk_bf16(v[2], v[3]);
;             *(u32x2*)(kdst + cb * 16 + fq * 4) = w; }
; #pragma unroll
;         for (int cb = 4; cb < 8; ++cb)
; #pragma unroll
;             for (int q = 0; q < 4; ++q) VT[((size_t)(b * 4 + h) * 64 + (cb - 4) * 16 + fq * 4 + q) * NKEY + key] = tobf(acc[tb][cb][q]); }
	v_pk_mul_f32 v[44:45], v[44:45], v[56:57]
	v_pk_mul_f32 v[46:47], v[46:47], v[54:55]
	v_cvt_pk_bf16_f32 v44, v44, v45
	v_pk_mul_f32 v[56:57], v[78:79], v[48:49] op_sel_hi:[1,0]
	v_cvt_pk_bf16_f32 v45, v46, v47
	global_store_dwordx2 v[52:53], v[44:45], off offset:32
	global_load_dwordx4 v[44:47], v[100:101], off offset:128
	v_pk_mul_f32 v[54:55], v[80:81], v[48:49] op_sel_hi:[1,0]
	s_waitcnt vmcnt(0)
	v_pk_mul_f32 v[44:45], v[44:45], v[56:57]
	v_pk_mul_f32 v[46:47], v[46:47], v[54:55]
	v_cvt_pk_bf16_f32 v44, v44, v45
	v_pk_mul_f32 v[56:57], v[86:87], v[48:49] op_sel_hi:[1,0]
	v_cvt_pk_bf16_f32 v45, v46, v47
	global_store_dwordx2 v[52:53], v[44:45], off offset:64
	global_load_dwordx4 v[44:47], v[100:101], off offset:192
	v_pk_mul_f32 v[54:55], v[88:89], v[48:49] op_sel_hi:[1,0]
	s_waitcnt vmcnt(0)
	v_pk_mul_f32 v[44:45], v[56:57], v[44:45]
	v_pk_mul_f32 v[46:47], v[54:55], v[46:47]
	v_cvt_pk_bf16_f32 v44, v44, v45
	v_mov_b32_e32 v54, v186
	v_cvt_pk_bf16_f32 v45, v46, v47
	global_store_dwordx2 v[52:53], v[44:45], off offset:96
	global_load_dwordx4 v[44:47], v[100:101], off offset:256
	v_mov_b32_e32 v55, v188
	v_mov_b32_e32 v188, v187
	v_pk_mul_f32 v[54:55], v[48:49], v[54:55] op_sel_hi:[0,1]
	v_pk_mul_f32 v[56:57], v[48:49], v[188:189] op_sel_hi:[0,1]
	v_cvt_f32_ubyte0_e32 v49, v49
	v_mul_f32_e32 v58, v217, v49
	v_mul_f32_e32 v59, 0.15915494, v58
	v_cos_f32_e32 v58, v59
	v_sin_f32_e32 v60, v59
	v_mul_f32_e32 v59, v218, v49
	v_mul_f32_e32 v61, 0.15915494, v59
	v_cos_f32_e32 v59, v61
	v_sin_f32_e32 v61, v61
	s_waitcnt vmcnt(0)
	v_pk_mul_f32 v[44:45], v[54:55], v[44:45]
	ds_bpermute_b32 v54, v216, v44
	ds_bpermute_b32 v55, v216, v45
	v_pk_mul_f32 v[46:47], v[56:57], v[46:47]
	ds_bpermute_b32 v56, v216, v46
	ds_bpermute_b32 v57, v216, v47
	s_waitcnt lgkmcnt(0)
	v_pk_mul_f32 v[54:55], v[60:61], v[54:55]
	v_mul_f32_e32 v60, v219, v49
	v_mul_f32_e32 v49, v220, v49
	v_mul_f32_e32 v61, 0.15915494, v60
	v_mul_f32_e32 v49, 0.15915494, v49
	v_sin_f32_e32 v62, v61
	v_sin_f32_e32 v63, v49
	v_cos_f32_e32 v60, v61
	v_cos_f32_e32 v61, v49
	v_cndmask_b32_e64 v55, v55, -v55, s[36:37]
	v_pk_mul_f32 v[56:57], v[62:63], v[56:57]
	v_cndmask_b32_e64 v54, v54, -v54, s[36:37]
	v_cndmask_b32_e64 v57, v57, -v57, s[36:37]
	v_cndmask_b32_e64 v56, v56, -v56, s[36:37]
	v_pk_fma_f32 v[54:55], v[58:59], v[44:45], v[54:55]
	v_pk_fma_f32 v[56:57], v[60:61], v[46:47], v[56:57]
	v_cndmask_b32_e32 v44, v54, v44, vcc
	v_cndmask_b32_e32 v45, v55, v45, vcc
	v_cndmask_b32_e32 v46, v56, v46, vcc
	v_cndmask_b32_e32 v47, v57, v47, vcc
	v_cvt_pk_bf16_f32 v44, v44, v45
	v_cvt_pk_bf16_f32 v45, v46, v47
	global_store_dwordx2 v[52:53], v[44:45], off offset:128
	global_load_dwordx4 v[44:47], v[100:101], off offset:320
	v_cvt_f32_ubyte0_e32 v61, v64
	v_mul_f32_e32 v56, v217, v61
	v_pk_mul_f32 v[54:55], v[48:49], v[184:185] op_sel_hi:[0,1]
	v_mul_f32_e32 v57, 0.15915494, v56
	v_pk_mul_f32 v[48:49], v[48:49], v[174:175] op_sel_hi:[0,1]
	v_cos_f32_e32 v56, v57
	v_sin_f32_e32 v58, v57
	v_mul_f32_e32 v57, v218, v61
	v_mul_f32_e32 v59, 0.15915494, v57
	v_cos_f32_e32 v57, v59
	v_sin_f32_e32 v59, v59
	s_waitcnt vmcnt(0)
	v_pk_mul_f32 v[44:45], v[54:55], v[44:45]
	v_pk_mul_f32 v[46:47], v[48:49], v[46:47]
	ds_bpermute_b32 v48, v216, v44
	ds_bpermute_b32 v49, v216, v45
	ds_bpermute_b32 v54, v216, v46
	ds_bpermute_b32 v55, v216, v47
	s_waitcnt lgkmcnt(0)
	v_pk_mul_f32 v[48:49], v[58:59], v[48:49]
	v_mul_f32_e32 v58, v219, v61
	v_mul_f32_e32 v59, 0.15915494, v58
	v_cos_f32_e32 v58, v59
	v_sin_f32_e32 v60, v59
	v_mul_f32_e32 v59, v220, v61
	v_mul_f32_e32 v61, 0.15915494, v59
	v_cos_f32_e32 v59, v61
	v_sin_f32_e32 v61, v61
	v_cndmask_b32_e64 v49, v49, -v49, s[36:37]
	v_cndmask_b32_e64 v48, v48, -v48, s[36:37]
	v_pk_fma_f32 v[48:49], v[56:57], v[44:45], v[48:49]
	v_pk_mul_f32 v[54:55], v[60:61], v[54:55]
	v_cndmask_b32_e32 v44, v48, v44, vcc
	v_cndmask_b32_e64 v55, v55, -v55, s[36:37]
	v_cndmask_b32_e64 v54, v54, -v54, s[36:37]
	v_pk_fma_f32 v[54:55], v[58:59], v[46:47], v[54:55]
	v_cndmask_b32_e32 v45, v49, v45, vcc
	v_cndmask_b32_e32 v46, v54, v46, vcc
	v_cndmask_b32_e32 v47, v55, v47, vcc
	v_cvt_pk_bf16_f32 v44, v44, v45
	v_cvt_pk_bf16_f32 v45, v46, v47
	v_lshlrev_b64 v[46:47], 6, v[50:51]
	global_store_dwordx2 v[52:53], v[44:45], off offset:160
	v_lshl_add_u64 v[44:45], s[40:41], 0, v[0:1]
	v_or_b32_e32 v0, v46, v96
	v_mad_u64_u32 v[44:45], s[6:7], v0, s88, v[44:45]
	v_cvt_pk_bf16_f32 v46, v74, v1
	v_mad_i32_i24 v45, v47, s88, v45
	global_store_short v[44:45], v46, off
	v_add_co_u32_e64 v46, s[38:39], s19, v44
	v_cvt_pk_bf16_f32 v0, v75, v1
	s_nop 1
	v_addc_co_u32_e64 v47, s[38:39], 0, v45, s[38:39]
	global_store_short v[46:47], v0, off offset:512
	v_add_co_u32_e64 v46, s[38:39], s33, v44
	v_cvt_pk_bf16_f32 v0, v76, v1
	s_nop 1
	v_addc_co_u32_e64 v47, s[38:39], 0, v45, s[38:39]
	global_store_short v[46:47], v0, off offset:1024
	v_add_co_u32_e64 v46, s[38:39], s23, v44
	v_cvt_pk_bf16_f32 v0, v77, v1
	s_nop 1
	v_addc_co_u32_e64 v47, s[38:39], 0, v45, s[38:39]
	global_store_short v[46:47], v0, off offset:1536
	v_add_co_u32_e64 v46, s[38:39], s15, v44
	v_cvt_pk_bf16_f32 v0, v82, v1
	s_nop 1
	v_addc_co_u32_e64 v47, s[38:39], 0, v45, s[38:39]
	global_store_short v[46:47], v0, off
	v_add_co_u32_e64 v46, s[38:39], s24, v44
	v_cvt_pk_bf16_f32 v0, v83, v1
	s_nop 1
	v_addc_co_u32_e64 v47, s[38:39], 0, v45, s[38:39]
	global_store_short v[46:47], v0, off offset:512
	v_add_co_u32_e64 v46, s[38:39], s18, v44
	v_cvt_pk_bf16_f32 v0, v84, v1
	s_nop 1
	v_addc_co_u32_e64 v47, s[38:39], 0, v45, s[38:39]
	global_store_short v[46:47], v0, off offset:1024
	v_add_co_u32_e64 v46, s[38:39], s25, v44
	v_cvt_pk_bf16_f32 v0, v85, v1
; __device__ __forceinline__ unsigned cvt_pk_bf16(float lo, float hi) { unsigned r; asm volatile("v_cvt_pk_bf16_f32 %0, %1, %2" : "=v"(r) : "v"(lo), "v"(hi)); return r; }
; __device__ __forceinline__ bf16_t tobf(float f) { return (bf16_t)(cvt_pk_bf16(f, 0.f) & 0xffffu); }
; __device__ __forceinline__ void kvproj_task(int t, int l, const float* kvnorm, const float* kgain, const bf16_t* P, const bf16_t* WUKV, bf16_t* KB, bf16_t* VT, int fr, int fq) {
;     ...
;     for (int tb = 0; tb < 2; ++tb) { const int row = row0 + tb * 16, rr = isc ? row - ML : row;
;         const int b = isc ? rr >> 8 : rr >> 11, tpos = isc ? rr & 255 : rr & 2047, key = isc ? tpos : 256 + tpos;
;         float s2 = skr[tb];
; #pragma unroll
;         for (int cb = 0; cb < 4; ++cb) s2 += (acc[tb][cb][0] * acc[tb][cb][0] + acc[tb][cb][1] * acc[tb][cb][1]) + (acc[tb][cb][2] * acc[tb][cb][2] + acc[tb][cb][3] * acc[tb][cb][3]);
;         s2 += __shfl_xor(s2, 16); s2 += __shfl_xor(s2, 32);
;         const float rh = rsqrtf(s2 * (1.f / 96.f) + EPS);
;         bf16_t* kdst = KB + ((size_t)(b * 4 + h) * NKEY + key) * 96;
; #pragma unroll
;         for (int cb = 0; cb < 6; ++cb) { const f32x4 kg = *(const f32x4*)(kgain + l * 96 + cb * 16 + fq * 4); f32x4 v = (cb < 4 ? acc[tb][cb < 4 ? cb : 0] : kr[tb][cb >= 4 ? cb - 4 : 0]) * rh * kg;
;             if (cb >= 4) { const f32x4 rv = rope16(v, fq, (float)(cb == 4 ? (tpos >> 6) : (tpos & 63))); if (!isc) v = rv; }
;             u32x2 w; w.x = cvt_pk_bf16(v[0], v[1]); w.y = cvt_pk_bf16(v[2], v[3]);
;             *(u32x2*)(kdst + cb * 16 + fq * 4) = w; }
; #pragma unroll
;         for (int cb = 4; cb < 8; ++cb)
; #pragma unroll
;             for (int q = 0; q < 4; ++q) VT[((size_t)(b * 4 + h) * 64 + (cb - 4) * 16 + fq * 4 + q) * NKEY + key] = tobf(acc[tb][cb][q]); }
	s_nop 1
	v_addc_co_u32_e64 v47, s[38:39], 0, v45, s[38:39]
	global_store_short v[46:47], v0, off offset:1536
	v_add_co_u32_e64 v46, s[38:39], s26, v44
	v_cvt_pk_bf16_f32 v0, v90, v1
	s_nop 1
	v_addc_co_u32_e64 v47, s[38:39], 0, v45, s[38:39]
	global_store_short v[46:47], v0, off
	v_add_co_u32_e64 v46, s[38:39], s27, v44
	v_cvt_pk_bf16_f32 v0, v91, v1
	s_nop 1
	v_addc_co_u32_e64 v47, s[38:39], 0, v45, s[38:39]
	global_store_short v[46:47], v0, off offset:512
	v_add_co_u32_e64 v46, s[38:39], s44, v44
	v_cvt_pk_bf16_f32 v0, v92, v1
	s_nop 1
	v_addc_co_u32_e64 v47, s[38:39], 0, v45, s[38:39]
	global_store_short v[46:47], v0, off offset:1024
	v_add_co_u32_e64 v46, s[38:39], s45, v44
	v_cvt_pk_bf16_f32 v0, v93, v1
	s_nop 1
	v_addc_co_u32_e64 v47, s[38:39], 0, v45, s[38:39]
	global_store_short v[46:47], v0, off offset:1536
	v_add_co_u32_e64 v46, s[38:39], s46, v44
	v_cvt_pk_bf16_f32 v0, v38, v1
	s_nop 1
	v_addc_co_u32_e64 v47, s[38:39], 0, v45, s[38:39]
	v_add_co_u32_e64 v38, s[38:39], s48, v44
	global_store_short v[46:47], v0, off
	v_cvt_pk_bf16_f32 v0, v39, v1
	s_nop 0
	v_addc_co_u32_e64 v39, s[38:39], 0, v45, s[38:39]
	global_store_short v[38:39], v0, off offset:512
	v_add_co_u32_e64 v38, s[38:39], s51, v44
	v_cvt_pk_bf16_f32 v0, v40, v1
	v_pk_add_f32 v[46:47], v[192:193], v[192:193] op_sel:[0,1] op_sel_hi:[1,0]
	s_nop 0
	v_addc_co_u32_e64 v39, s[38:39], 0, v45, s[38:39]
	global_store_short v[38:39], v0, off offset:1024
	v_add_co_u32_e64 v38, s[38:39], s52, v44
	v_cvt_pk_bf16_f32 v0, v41, v1
	s_nop 1
	v_addc_co_u32_e64 v39, s[38:39], 0, v45, s[38:39]
	global_store_short v[38:39], v0, off offset:1536
	v_add_u32_e32 v0, 0xffffc010, v171
	v_cndmask_b32_e32 v39, v173, v0, vcc
	v_mul_f32_e32 v0, v4, v4
	v_mov_b32_e32 v47, v0
	v_mul_f32_e32 v0, v179, v179
	v_and_b32_e32 v44, v39, v43
	v_mul_f32_e32 v43, v5, v5
	v_mov_b32_e32 v173, v3
	v_pk_fma_f32 v[48:49], v[178:179], v[178:179], v[0:1] op_sel_hi:[1,1,0]
	v_mov_b32_e32 v171, v2
	v_pk_mul_f32 v[40:41], v[172:173], v[172:173]
	v_mov_b32_e32 v49, v43
	v_pk_fma_f32 v[40:41], v[170:171], v[170:171], v[40:41]
	v_pk_add_f32 v[46:47], v[46:47], v[48:49]
	v_pk_mul_f32 v[48:49], v[6:7], v[6:7]
	v_pk_add_f32 v[40:41], v[40:41], v[46:47]
	v_pk_mul_f32 v[46:47], v[8:9], v[8:9]
	v_mul_f32_e32 v0, v26, v26
	v_pk_mov_b32 v[50:51], v[48:49], v[46:47] op_sel:[1,0]
	v_mov_b32_e32 v49, v47
	v_pk_add_f32 v[46:47], v[50:51], v[48:49]
	v_mul_f32_e32 v43, v27, v27
	v_pk_add_f32 v[40:41], v[40:41], v[40:41] op_sel:[0,1] op_sel_hi:[1,0]
	v_pk_add_f32 v[46:47], v[46:47], v[46:47] op_sel:[0,1] op_sel_hi:[1,0]
	v_mov_b32_e32 v41, v0
	v_mov_b32_e32 v47, v43
	v_mul_f32_e32 v0, v19, v19
	v_pk_add_f32 v[40:41], v[40:41], v[46:47]
	v_pk_fma_f32 v[46:47], v[18:19], v[18:19], v[0:1] op_sel_hi:[1,1,0]
	v_mul_f32_e32 v0, v21, v21
	v_mul_f32_e32 v45, v28, v28
	v_mul_f32_e32 v50, v29, v29
	v_pk_fma_f32 v[48:49], v[20:21], v[20:21], v[0:1] op_sel_hi:[1,1,0]
	v_mov_b32_e32 v47, v45
	v_mov_b32_e32 v49, v50
	v_pk_add_f32 v[46:47], v[46:47], v[48:49]
	v_add_u32_e32 v38, 0x100, v44
	v_pk_add_f32 v[40:41], v[40:41], v[46:47]
	v_cndmask_b32_e32 v0, v38, v44, vcc
	v_add_f32_e32 v40, v40, v41
	ds_bpermute_b32 v38, v215, v40
	v_ashrrev_i32_e32 v41, v42, v39
	v_lshrrev_b32_e32 v44, 6, v44
	v_mov_b32_e32 v171, v172
	s_waitcnt lgkmcnt(0)
	v_add_f32_e32 v38, v40, v38
	ds_bpermute_b32 v40, v216, v38
	s_waitcnt lgkmcnt(0)
	v_add_f32_e32 v38, v38, v40
	v_fmamk_f32 v38, v38, 0x3c2aaaab, v197
	v_cmp_gt_f32_e64 s[38:39], s47, v38
	v_mul_f32_e32 v40, 0x4b800000, v38
	s_nop 0
	v_cndmask_b32_e64 v38, v38, v40, s[38:39]
	v_rsq_f32_e32 v38, v38
	s_nop 0
	v_mul_f32_e32 v40, 0x45800000, v38
	v_cndmask_b32_e64 v38, v38, v40, s[38:39]
	v_lshl_or_b32 v40, v41, 2, s22
	v_mad_i64_i32 v[46:47], s[6:7], v40, s9, v[0:1]
	v_mad_u64_u32 v[42:43], s[6:7], v46, s14, v[102:103]
	v_mad_i32_i24 v43, v47, s14, v43
	global_load_dwordx4 v[46:49], v[100:101], off
	v_pk_mul_f32 v[2:3], v[2:3], v[38:39] op_sel_hi:[1,0]
	v_pk_mul_f32 v[4:5], v[4:5], v[38:39] op_sel_hi:[1,0]
	v_pk_mul_f32 v[6:7], v[6:7], v[38:39] op_sel_hi:[1,0]
	v_pk_mul_f32 v[8:9], v[8:9], v[38:39] op_sel_hi:[1,0]
	v_ashrrev_i32_e32 v41, 31, v40
	v_lshlrev_b32_e32 v0, 1, v0
	s_waitcnt vmcnt(0)
	v_pk_mul_f32 v[2:3], v[46:47], v[2:3]
	v_pk_mul_f32 v[4:5], v[48:49], v[4:5]
	v_cvt_pk_bf16_f32 v2, v2, v3
	s_nop 0
	v_cvt_pk_bf16_f32 v3, v4, v5
	global_store_dwordx2 v[42:43], v[2:3], off
	global_load_dwordx4 v[2:5], v[100:101], off offset:64
	s_waitcnt vmcnt(0)
	v_pk_mul_f32 v[2:3], v[2:3], v[6:7]
	v_pk_mul_f32 v[4:5], v[4:5], v[8:9]
	v_cvt_pk_bf16_f32 v2, v2, v3
	v_pk_mul_f32 v[8:9], v[18:19], v[38:39] op_sel_hi:[1,0]
	v_cvt_pk_bf16_f32 v3, v4, v5
	global_store_dwordx2 v[42:43], v[2:3], off offset:32
	global_load_dwordx4 v[2:5], v[100:101], off offset:128
	v_pk_mul_f32 v[6:7], v[20:21], v[38:39] op_sel_hi:[1,0]
	s_waitcnt vmcnt(0)
	v_pk_mul_f32 v[2:3], v[2:3], v[8:9]
	v_pk_mul_f32 v[4:5], v[4:5], v[6:7]
	v_cvt_pk_bf16_f32 v2, v2, v3
	v_pk_mul_f32 v[8:9], v[26:27], v[38:39] op_sel_hi:[1,0]
	v_cvt_pk_bf16_f32 v3, v4, v5
	global_store_dwordx2 v[42:43], v[2:3], off offset:64
	global_load_dwordx4 v[2:5], v[100:101], off offset:192
	v_pk_mul_f32 v[6:7], v[28:29], v[38:39] op_sel_hi:[1,0]
	v_cvt_f32_ubyte0_e32 v27, v44
	v_mul_f32_e32 v18, v217, v27
	v_mul_f32_e32 v19, 0.15915494, v18
	v_cos_f32_e32 v18, v19
	v_sin_f32_e32 v20, v19
	v_mul_f32_e32 v19, v218, v27
	v_mul_f32_e32 v21, 0.15915494, v19
	v_cos_f32_e32 v19, v21
	v_sin_f32_e32 v21, v21
	s_waitcnt vmcnt(0)
; __device__ __forceinline__ unsigned cvt_pk_bf16(float lo, float hi) { unsigned r; asm volatile("v_cvt_pk_bf16_f32 %0, %1, %2" : "=v"(r) : "v"(lo), "v"(hi)); return r; }
; __device__ __forceinline__ bf16_t tobf(float f) { return (bf16_t)(cvt_pk_bf16(f, 0.f) & 0xffffu); }
; __device__ __forceinline__ void kvproj_task(int t, int l, const float* kvnorm, const float* kgain, const bf16_t* P, const bf16_t* WUKV, bf16_t* KB, bf16_t* VT, int fr, int fq) {
;     ...
;         for (int cb = 0; cb < 6; ++cb) { const f32x4 kg = *(const f32x4*)(kgain + l * 96 + cb * 16 + fq * 4); f32x4 v = (cb < 4 ? acc[tb][cb < 4 ? cb : 0] : kr[tb][cb >= 4 ? cb - 4 : 0]) * rh * kg;
;             if (cb >= 4) { const f32x4 rv = rope16(v, fq, (float)(cb == 4 ? (tpos >> 6) : (tpos & 63))); if (!isc) v = rv; }
;             u32x2 w; w.x = cvt_pk_bf16(v[0], v[1]); w.y = cvt_pk_bf16(v[2], v[3]);
;             *(u32x2*)(kdst + cb * 16 + fq * 4) = w; }
; #pragma unroll
;         for (int cb = 4; cb < 8; ++cb)
; #pragma unroll
;             for (int q = 0; q < 4; ++q) VT[((size_t)(b * 4 + h) * 64 + (cb - 4) * 16 + fq * 4 + q) * NKEY + key] = tobf(acc[tb][cb][q]); }
	v_pk_mul_f32 v[2:3], v[8:9], v[2:3]
	v_pk_mul_f32 v[4:5], v[6:7], v[4:5]
	v_cvt_pk_bf16_f32 v2, v2, v3
	v_mov_b32_e32 v6, v180
	v_cvt_pk_bf16_f32 v3, v4, v5
	global_store_dwordx2 v[42:43], v[2:3], off offset:96
	global_load_dwordx4 v[2:5], v[100:101], off offset:256
	v_mov_b32_e32 v7, v182
	v_pk_mul_f32 v[6:7], v[38:39], v[6:7] op_sel_hi:[0,1]
	v_mov_b32_e32 v182, v181
	v_pk_mul_f32 v[8:9], v[38:39], v[182:183] op_sel_hi:[0,1]
	s_waitcnt vmcnt(0)
	v_pk_mul_f32 v[2:3], v[6:7], v[2:3]
	ds_bpermute_b32 v6, v216, v2
	ds_bpermute_b32 v7, v216, v3
	v_pk_mul_f32 v[4:5], v[8:9], v[4:5]
	ds_bpermute_b32 v8, v216, v4
	ds_bpermute_b32 v9, v216, v5
	s_waitcnt lgkmcnt(0)
	v_pk_mul_f32 v[6:7], v[20:21], v[6:7]
	v_mul_f32_e32 v20, v219, v27
	v_mul_f32_e32 v21, 0.15915494, v20
	v_cos_f32_e32 v20, v21
	v_sin_f32_e32 v26, v21
	v_mul_f32_e32 v21, v220, v27
	v_mul_f32_e32 v27, 0.15915494, v21
	v_cos_f32_e32 v21, v27
	v_sin_f32_e32 v27, v27
	v_cndmask_b32_e64 v7, v7, -v7, s[36:37]
	v_cndmask_b32_e64 v6, v6, -v6, s[36:37]
	v_pk_fma_f32 v[6:7], v[18:19], v[2:3], v[6:7]
	v_pk_mul_f32 v[8:9], v[26:27], v[8:9]
	v_cndmask_b32_e32 v2, v6, v2, vcc
	v_cndmask_b32_e64 v9, v9, -v9, s[36:37]
	v_cndmask_b32_e64 v8, v8, -v8, s[36:37]
	v_pk_fma_f32 v[8:9], v[20:21], v[4:5], v[8:9]
	v_cndmask_b32_e32 v3, v7, v3, vcc
	v_cndmask_b32_e32 v4, v8, v4, vcc
	v_cndmask_b32_e32 v5, v9, v5, vcc
	v_cvt_pk_bf16_f32 v2, v2, v3
	v_cvt_pk_bf16_f32 v3, v4, v5
	global_store_dwordx2 v[42:43], v[2:3], off offset:128
	global_load_dwordx4 v[2:5], v[100:101], off offset:320
	v_and_b32_e32 v18, 63, v39
	v_cvt_f32_ubyte0_e32 v27, v18
	v_mul_f32_e32 v18, v217, v27
	v_pk_mul_f32 v[6:7], v[38:39], v[178:179] op_sel_hi:[0,1]
	v_mul_f32_e32 v19, 0.15915494, v18
	v_cos_f32_e32 v18, v19
	v_sin_f32_e32 v20, v19
	v_mul_f32_e32 v19, v218, v27
	v_mul_f32_e32 v21, 0.15915494, v19
	v_cos_f32_e32 v19, v21
	v_sin_f32_e32 v21, v21
	v_pk_mul_f32 v[8:9], v[38:39], v[170:171] op_sel_hi:[0,1]
	s_waitcnt vmcnt(0)
	v_pk_mul_f32 v[2:3], v[6:7], v[2:3]
	ds_bpermute_b32 v6, v216, v2
	ds_bpermute_b32 v7, v216, v3
	v_pk_mul_f32 v[4:5], v[8:9], v[4:5]
	ds_bpermute_b32 v8, v216, v4
	ds_bpermute_b32 v9, v216, v5
	s_waitcnt lgkmcnt(0)
	v_pk_mul_f32 v[6:7], v[20:21], v[6:7]
	v_mul_f32_e32 v20, v219, v27
	v_mul_f32_e32 v21, 0.15915494, v20
	v_cos_f32_e32 v20, v21
	v_sin_f32_e32 v26, v21
	v_mul_f32_e32 v21, v220, v27
	v_mul_f32_e32 v27, 0.15915494, v21
	v_cos_f32_e32 v21, v27
	v_sin_f32_e32 v27, v27
	v_cndmask_b32_e64 v7, v7, -v7, s[36:37]
	v_cndmask_b32_e64 v6, v6, -v6, s[36:37]
	v_pk_fma_f32 v[6:7], v[18:19], v[2:3], v[6:7]
	v_pk_mul_f32 v[8:9], v[26:27], v[8:9]
	v_cndmask_b32_e32 v2, v6, v2, vcc
	v_cndmask_b32_e64 v9, v9, -v9, s[36:37]
	v_cndmask_b32_e64 v8, v8, -v8, s[36:37]
	v_pk_fma_f32 v[8:9], v[20:21], v[4:5], v[8:9]
	v_cndmask_b32_e32 v3, v7, v3, vcc
	v_cndmask_b32_e32 v4, v8, v4, vcc
	v_cndmask_b32_e32 v5, v9, v5, vcc
	v_cvt_pk_bf16_f32 v2, v2, v3
	v_cvt_pk_bf16_f32 v3, v4, v5
	v_lshlrev_b64 v[4:5], 6, v[40:41]
	global_store_dwordx2 v[42:43], v[2:3], off offset:160
	v_lshl_add_u64 v[2:3], s[40:41], 0, v[0:1]
	v_or_b32_e32 v0, v4, v96
	v_mad_u64_u32 v[2:3], s[6:7], v0, s88, v[2:3]
	v_cvt_pk_bf16_f32 v4, v14, v1
	v_mad_i32_i24 v3, v5, s88, v3
	global_store_short v[2:3], v4, off
	v_add_co_u32_e32 v4, vcc, s19, v2
	v_cvt_pk_bf16_f32 v0, v15, v1
	s_nop 1
	v_addc_co_u32_e32 v5, vcc, 0, v3, vcc
	global_store_short v[4:5], v0, off offset:512
	v_add_co_u32_e32 v4, vcc, s33, v2
	v_cvt_pk_bf16_f32 v0, v16, v1
	s_nop 1
	v_addc_co_u32_e32 v5, vcc, 0, v3, vcc
	global_store_short v[4:5], v0, off offset:1024
	v_add_co_u32_e32 v4, vcc, s23, v2
	v_cvt_pk_bf16_f32 v0, v17, v1
	s_nop 1
	v_addc_co_u32_e32 v5, vcc, 0, v3, vcc
	global_store_short v[4:5], v0, off offset:1536
	v_add_co_u32_e32 v4, vcc, s15, v2
	v_cvt_pk_bf16_f32 v0, v22, v1
	s_nop 1
	v_addc_co_u32_e32 v5, vcc, 0, v3, vcc
	global_store_short v[4:5], v0, off
	v_add_co_u32_e32 v4, vcc, s24, v2
	v_cvt_pk_bf16_f32 v0, v23, v1
	s_nop 1
	v_addc_co_u32_e32 v5, vcc, 0, v3, vcc
	global_store_short v[4:5], v0, off offset:512
	v_add_co_u32_e32 v4, vcc, s18, v2
	v_cvt_pk_bf16_f32 v0, v24, v1
	s_nop 1
	v_addc_co_u32_e32 v5, vcc, 0, v3, vcc
	global_store_short v[4:5], v0, off offset:1024
	v_add_co_u32_e32 v4, vcc, s25, v2
	v_cvt_pk_bf16_f32 v0, v25, v1
	s_nop 1
	v_addc_co_u32_e32 v5, vcc, 0, v3, vcc
	global_store_short v[4:5], v0, off offset:1536
	v_add_co_u32_e32 v4, vcc, s26, v2
	v_cvt_pk_bf16_f32 v0, v30, v1
	s_nop 1
	v_addc_co_u32_e32 v5, vcc, 0, v3, vcc
	global_store_short v[4:5], v0, off
	v_add_co_u32_e32 v4, vcc, s27, v2
	v_cvt_pk_bf16_f32 v0, v31, v1
	s_nop 1
	v_addc_co_u32_e32 v5, vcc, 0, v3, vcc
	global_store_short v[4:5], v0, off offset:512
	v_add_co_u32_e32 v4, vcc, s44, v2
	v_cvt_pk_bf16_f32 v0, v32, v1
	s_nop 1
	v_addc_co_u32_e32 v5, vcc, 0, v3, vcc
	global_store_short v[4:5], v0, off offset:1024
	v_add_co_u32_e32 v4, vcc, s45, v2
	v_cvt_pk_bf16_f32 v0, v33, v1
	s_nop 1
	v_addc_co_u32_e32 v5, vcc, 0, v3, vcc
	global_store_short v[4:5], v0, off offset:1536
	v_add_co_u32_e32 v4, vcc, s46, v2
	v_cvt_pk_bf16_f32 v0, v34, v1
	s_nop 1
	v_addc_co_u32_e32 v5, vcc, 0, v3, vcc
	global_store_short v[4:5], v0, off
	v_add_co_u32_e32 v4, vcc, s48, v2
	v_cvt_pk_bf16_f32 v0, v35, v1
	s_nop 1
	v_addc_co_u32_e32 v5, vcc, 0, v3, vcc
	global_store_short v[4:5], v0, off offset:512
	v_add_co_u32_e32 v4, vcc, 0x38000, v2
	v_cvt_pk_bf16_f32 v0, v36, v1
	s_nop 1
	v_addc_co_u32_e32 v5, vcc, 0, v3, vcc
	v_add_co_u32_e32 v2, vcc, 0x39000, v2
	global_store_short v[4:5], v0, off offset:1024
	s_nop 0
	v_addc_co_u32_e32 v3, vcc, 0, v3, vcc
	v_cvt_pk_bf16_f32 v0, v37, v1
	global_store_short v[2:3], v0, off offset:1536
	s_cbranch_scc0 .LBB0_422

; __device__ __forceinline__ unsigned cvt_pk_bf16(float lo, float hi) { unsigned r; asm volatile("v_cvt_pk_bf16_f32 %0, %1, %2" : "=v"(r) : "v"(lo), "v"(hi)); return r; }
; __device__ __forceinline__ float bflo(unsigned w) { return __uint_as_float(w << 16); }
; __device__ __forceinline__ float bfhi(unsigned w) { return __uint_as_float(w & 0xffff0000u); }
; #define UNPK8(VV_, XX_) float XX_[8] = {bflo((VV_).x), bfhi((VV_).x), bflo((VV_).y), bfhi((VV_).y), bflo((VV_).z), bfhi((VV_).z), bflo((VV_).w), bfhi((VV_).w)}
; __device__ __forceinline__ void kvproj_task(int t, int l, const float* kvnorm, const float* kgain, const bf16_t* P, const bf16_t* WUKV, bf16_t* KB, bf16_t* VT, int fr, int fq) {
;     ...
;     for (int tb = 0; tb < 2; ++tb) { const int row = row0 + tb * 16; float ss = 0.f; u32x4 raw[4];
; #pragma unroll
;         for (int ks = 0; ks < 4; ++ks) { raw[ks] = ld8(P + (size_t)row * INP + ks * 32 + fq * 8); UNPK8(raw[ks], x);
;             ss += (x[0] * x[0] + x[1] * x[1]) + (x[2] * x[2] + x[3] * x[3]) + (x[4] * x[4] + x[5] * x[5]) + (x[6] * x[6] + x[7] * x[7]); }
; #pragma unroll
;         for (int cbr = 0; cbr < 2; ++cbr) { const u32x2 w = ld4(P + (size_t)row * INP + OFF_KROPE + cbr * 16 + fq * 4); kr[tb][cbr] = (f32x4){bflo(w.x), bfhi(w.x), bflo(w.y), bfhi(w.y)}; }
;         ss += __shfl_xor(ss, 16); ss += __shfl_xor(ss, 32);
;         const float rinv = rsqrtf(ss * (1.f / 128.f) + EPS);
; #pragma unroll
;         for (int ks = 0; ks < 4; ++ks) { const float* gp = kvnorm + l * 128 + ks * 32 + fq * 8; const f32x4 g0 = *(const f32x4*)gp, g1 = *(const f32x4*)(gp + 4); UNPK8(raw[ks], x); u32x4 o;
;             o.x = cvt_pk_bf16(x[0] * rinv * g0[0], x[1] * rinv * g0[1]); o.y = cvt_pk_bf16(x[2] * rinv * g0[2], x[3] * rinv * g0[3]);
;             o.z = cvt_pk_bf16(x[4] * rinv * g1[0], x[5] * rinv * g1[1]); o.w = cvt_pk_bf16(x[6] * rinv * g1[2], x[7] * rinv * g1[3]);
;             bfr[tb][ks] = asfrag(o); }
.LBB0_427:
	s_and_b32 s1, s5, 0xffffffe0
	v_or_b32_e32 v109, s1, v97
	v_mad_i64_i32 v[6:7], s[6:7], v109, s84, v[94:95]
	global_load_dwordx4 v[14:17], v[6:7], off
	global_load_dwordx4 v[2:5], v[6:7], off offset:64
	global_load_dwordx4 v[40:43], v[6:7], off offset:128
	global_load_dwordx4 v[50:53], v[6:7], off offset:192
	v_or_b32_e32 v111, 16, v109
	s_and_b32 s1, s4, 3
	s_add_i32 s4, s4, s14
	s_waitcnt vmcnt(0) lgkmcnt(0)
	v_and_b32_e32 v25, 0xffff0000, v15
	v_and_b32_e32 v29, 0xffff0000, v3
	v_and_b32_e32 v28, 0xffff0000, v2
	v_lshlrev_b32_e32 v31, 16, v3
	v_lshlrev_b32_e32 v30, 16, v2
	v_pk_mul_f32 v[2:3], v[28:29], v[28:29]
	v_and_b32_e32 v21, 0xffff0000, v5
	v_and_b32_e32 v20, 0xffff0000, v4
	v_pk_fma_f32 v[2:3], v[30:31], v[30:31], v[2:3]
	v_lshlrev_b32_e32 v27, 16, v5
	v_lshlrev_b32_e32 v26, 16, v4
	v_pk_mul_f32 v[4:5], v[20:21], v[20:21]
	v_pk_add_f32 v[2:3], v[2:3], v[2:3] op_sel:[0,1] op_sel_hi:[1,0]
	v_pk_fma_f32 v[44:45], v[26:27], v[26:27], v[4:5]
	v_and_b32_e32 v39, 0xffff0000, v14
	v_pk_add_f32 v[54:55], v[44:45], v[2:3]
	v_mad_i64_i32 v[2:3], s[6:7], v109, s84, v[106:107]
	global_load_dwordx2 v[4:5], v[2:3], off offset:256
	s_nop 0
	global_load_dwordx2 v[2:3], v[2:3], off offset:288
	v_and_b32_e32 v38, 0xffff0000, v16
	v_lshlrev_b32_e32 v24, 16, v15
	v_mul_f32_e32 v0, v25, v25
	v_lshlrev_b32_e32 v18, 16, v40
	v_and_b32_e32 v19, 0xffff0000, v40
	v_lshlrev_b32_e32 v8, 16, v41
	v_and_b32_e32 v9, 0xffff0000, v41
	v_lshlrev_b32_e32 v41, 16, v14
	v_lshlrev_b32_e32 v40, 16, v16
	v_pk_mul_f32 v[14:15], v[38:39], v[38:39]
	v_pk_fma_f32 v[22:23], v[24:25], v[24:25], v[0:1] op_sel_hi:[1,1,0]
	v_lshlrev_b32_e32 v7, 16, v53
	v_pk_fma_f32 v[14:15], v[40:41], v[40:41], v[14:15]
	v_mul_f32_e32 v6, v19, v19
	v_lshlrev_b32_e32 v36, 16, v17
	v_and_b32_e32 v37, 0xffff0000, v17
	v_lshlrev_b32_e32 v48, 16, v51
	v_and_b32_e32 v47, 0xffff0000, v51
	v_pk_add_f32 v[16:17], v[14:15], v[22:23] op_sel:[1,0] op_sel_hi:[0,1]
	v_lshlrev_b32_e32 v35, 16, v50
	v_and_b32_e32 v33, 0xffff0000, v50
	v_pk_fma_f32 v[50:51], v[18:19], v[18:19], v[6:7] op_sel_hi:[1,1,0]
	v_mul_f32_e32 v6, v9, v9
	v_and_b32_e32 v0, 0xffff0000, v53
	v_mul_f32_e32 v46, v48, v48
	v_mul_f32_e32 v49, v47, v47
	v_pk_add_f32 v[22:23], v[14:15], v[16:17]
	v_and_b32_e32 v32, 0xffff0000, v42
	v_pk_mov_b32 v[14:15], v[42:43], v[52:53] op_sel:[1,0]
	v_lshlrev_b32_e32 v17, 16, v52
	v_pk_fma_f32 v[52:53], v[8:9], v[8:9], v[6:7] op_sel_hi:[1,1,0]
	v_lshlrev_b32_e32 v34, 16, v42
	v_lshlrev_b32_e32 v16, 16, v43
	v_pk_mul_f32 v[42:43], v[32:33], v[32:33]
	v_mov_b32_e32 v51, v46
	v_mov_b32_e32 v53, v49
	v_and_b32_e32 v15, 0xffff0000, v15
	v_and_b32_e32 v14, 0xffff0000, v14
	v_pk_fma_f32 v[42:43], v[34:35], v[34:35], v[42:43]
	v_pk_add_f32 v[50:51], v[50:51], v[52:53]
	v_mul_f32_e32 v6, v37, v37
	v_pk_add_f32 v[42:43], v[42:43], v[50:51]
	v_pk_mul_f32 v[50:51], v[14:15], v[14:15]
	v_mov_b32_e32 v52, v22
	v_pk_fma_f32 v[50:51], v[16:17], v[16:17], v[50:51]
	v_mov_b32_e32 v53, v7
	v_pk_add_f32 v[42:43], v[50:51], v[42:43]
	v_pk_fma_f32 v[50:51], v[36:37], v[36:37], v[6:7] op_sel_hi:[1,1,0]
	v_mul_f32_e32 v56, v0, v0
	v_mov_b32_e32 v6, v50
	v_pk_add_f32 v[22:23], v[50:51], v[22:23]
	v_pk_mul_f32 v[50:51], v[6:7], v[52:53]
	v_pk_add_f32 v[44:45], v[44:45], v[54:55] op_sel:[1,0] op_sel_hi:[0,1]
	v_mov_b32_e32 v23, v51
	v_mov_b32_e32 v45, v56
	v_pk_add_f32 v[22:23], v[22:23], v[44:45]
	s_waitcnt vmcnt(0) lgkmcnt(0)
	v_and_b32_e32 v129, 0xffff0000, v5
	v_pk_add_f32 v[22:23], v[22:23], v[42:43]
	s_nop 0
	s_nop 0
	s_nop 0
	s_nop 0
	v_lshlrev_b32_e32 v120, 16, v3
	v_and_b32_e32 v122, 0xffff0000, v3
	v_add_f32_e32 v3, v22, v23
	ds_bpermute_b32 v6, v132, v3
	v_and_b32_e32 v128, 0xffff0000, v4
	v_lshlrev_b32_e32 v127, 16, v5
	v_lshlrev_b32_e32 v126, 16, v4
	v_pk_mul_f32 v[4:5], v[128:129], v[128:129]
	s_waitcnt lgkmcnt(0)
	v_add_f32_e32 v3, v3, v6
	ds_bpermute_b32 v6, v133, v3
	v_pk_fma_f32 v[130:131], v[126:127], v[126:127], v[4:5]
	v_lshlrev_b32_e32 v124, 16, v2
	v_and_b32_e32 v125, 0xffff0000, v2
	s_waitcnt lgkmcnt(0)
	v_add_f32_e32 v3, v3, v6
	v_fmamk_f32 v3, v3, 0x3c000000, v197
	v_cmp_gt_f32_e32 vcc, s47, v3
	v_mul_f32_e32 v6, 0x4b800000, v3
	s_nop 0
	v_cndmask_b32_e32 v3, v3, v6, vcc
	v_rsq_f32_e32 v3, v3
	s_nop 0
	v_mul_f32_e32 v6, 0x45800000, v3
	v_cndmask_b32_e32 v3, v3, v6, vcc
	v_mul_f32_e32 v6, v3, v41
	v_mul_f32_e32 v22, v3, v39
	v_mul_f32_e32 v23, v3, v25
	v_mul_f32_e32 v25, v3, v37
	v_mul_f32_e32 v28, v3, v28
	v_mul_f32_e32 v20, v3, v20
	v_mul_f32_e32 v0, v3, v0
	s_waitcnt vmcnt(1)
	v_mul_f32_e32 v25, v221, v25
	s_waitcnt vmcnt(0)
	v_mul_f32_e32 v6, v214, v6
	v_mul_f32_e32 v22, v215, v22
	v_cvt_pk_bf16_f32 v22, v6, v22
	v_mul_f32_e32 v6, v3, v24
	v_mul_f32_e32 v6, v216, v6
	v_mul_f32_e32 v23, v217, v23
	v_cvt_pk_bf16_f32 v23, v6, v23
	v_mul_f32_e32 v6, v3, v40
	v_mul_f32_e32 v24, v3, v38
	v_mul_f32_e32 v6, v218, v6
	v_mul_f32_e32 v24, v219, v24
	v_cvt_pk_bf16_f32 v24, v6, v24
	v_mul_f32_e32 v6, v3, v36
	v_mul_f32_e32 v6, v220, v6
	v_cvt_pk_bf16_f32 v25, v6, v25
	s_nop 0
	s_nop 0
	s_nop 0
	s_nop 0
	v_mul_f32_e32 v6, v3, v30
	s_waitcnt vmcnt(1)
	v_mul_f32_e32 v20, v227, v20
	s_waitcnt vmcnt(0)
	v_mul_f32_e32 v6, v222, v6
	v_mul_f32_e32 v28, v223, v28
	v_cvt_pk_bf16_f32 v38, v6, v28
	v_mul_f32_e32 v6, v3, v31
	v_mul_f32_e32 v6, v224, v6
	v_mul_f32_e32 v28, v3, v29
	v_mul_f32_e32 v28, v225, v28
	v_cvt_pk_bf16_f32 v39, v6, v28
	v_mul_f32_e32 v6, v3, v26
	v_mul_f32_e32 v6, v226, v6
	v_cvt_pk_bf16_f32 v40, v6, v20
	v_mul_f32_e32 v6, v3, v27
	v_mul_f32_e32 v20, v3, v21
	v_mul_f32_e32 v6, v228, v6
	v_mul_f32_e32 v20, v229, v20
	v_cvt_pk_bf16_f32 v41, v6, v20
	s_nop 0
	s_nop 0
	s_nop 0
	s_nop 0
	v_mul_f32_e32 v6, v3, v18
	v_mul_f32_e32 v18, v3, v19
	s_waitcnt vmcnt(0)
; __device__ __forceinline__ unsigned cvt_pk_bf16(float lo, float hi) { unsigned r; asm volatile("v_cvt_pk_bf16_f32 %0, %1, %2" : "=v"(r) : "v"(lo), "v"(hi)); return r; }
; __device__ __forceinline__ float bflo(unsigned w) { return __uint_as_float(w << 16); }
; __device__ __forceinline__ float bfhi(unsigned w) { return __uint_as_float(w & 0xffff0000u); }
; #define UNPK8(VV_, XX_) float XX_[8] = {bflo((VV_).x), bfhi((VV_).x), bflo((VV_).y), bfhi((VV_).y), bflo((VV_).z), bfhi((VV_).z), bflo((VV_).w), bfhi((VV_).w)}
; __device__ __forceinline__ void kvproj_task(int t, int l, const float* kvnorm, const float* kgain, const bf16_t* P, const bf16_t* WUKV, bf16_t* KB, bf16_t* VT, int fr, int fq) {
;     ...
;     for (int tb = 0; tb < 2; ++tb) { const int row = row0 + tb * 16; float ss = 0.f; u32x4 raw[4];
; #pragma unroll
;         for (int ks = 0; ks < 4; ++ks) { raw[ks] = ld8(P + (size_t)row * INP + ks * 32 + fq * 8); UNPK8(raw[ks], x);
;             ss += (x[0] * x[0] + x[1] * x[1]) + (x[2] * x[2] + x[3] * x[3]) + (x[4] * x[4] + x[5] * x[5]) + (x[6] * x[6] + x[7] * x[7]); }
; #pragma unroll
;         for (int cbr = 0; cbr < 2; ++cbr) { const u32x2 w = ld4(P + (size_t)row * INP + OFF_KROPE + cbr * 16 + fq * 4); kr[tb][cbr] = (f32x4){bflo(w.x), bfhi(w.x), bflo(w.y), bfhi(w.y)}; }
;         ss += __shfl_xor(ss, 16); ss += __shfl_xor(ss, 32);
;         const float rinv = rsqrtf(ss * (1.f / 128.f) + EPS);
; #pragma unroll
;         for (int ks = 0; ks < 4; ++ks) { const float* gp = kvnorm + l * 128 + ks * 32 + fq * 8; const f32x4 g0 = *(const f32x4*)gp, g1 = *(const f32x4*)(gp + 4); UNPK8(raw[ks], x); u32x4 o;
;             o.x = cvt_pk_bf16(x[0] * rinv * g0[0], x[1] * rinv * g0[1]); o.y = cvt_pk_bf16(x[2] * rinv * g0[2], x[3] * rinv * g0[3]);
;             o.z = cvt_pk_bf16(x[4] * rinv * g1[0], x[5] * rinv * g1[1]); o.w = cvt_pk_bf16(x[6] * rinv * g1[2], x[7] * rinv * g1[3]);
;             bfr[tb][ks] = asfrag(o); }
;         skr[tb] = (kr[tb][0][0] * kr[tb][0][0] + kr[tb][0][1] * kr[tb][0][1]) + (kr[tb][0][2] * kr[tb][0][2] + kr[tb][0][3] * kr[tb][0][3]) + (kr[tb][1][0] * kr[tb][1][0] + kr[tb][1][1] * kr[tb][1][1]) + (kr[tb][1][2] * kr[tb][1][2] + kr[tb][1][3] * kr[tb][1][3]); }
	v_mul_f32_e32 v6, v230, v6
	v_mul_f32_e32 v18, v231, v18
	v_cvt_pk_bf16_f32 v42, v6, v18
	v_mul_f32_e32 v6, v3, v8
	v_mul_f32_e32 v8, v3, v9
	v_mul_f32_e32 v6, v232, v6
	v_mul_f32_e32 v8, v233, v8
	v_cvt_pk_bf16_f32 v43, v6, v8
	v_mul_f32_e32 v6, v3, v34
	v_mul_f32_e32 v8, v3, v32
	v_mul_f32_e32 v6, v234, v6
	v_mul_f32_e32 v8, v235, v8
	v_cvt_pk_bf16_f32 v44, v6, v8
	v_mul_f32_e32 v6, v3, v16
	v_mul_f32_e32 v8, v3, v14
	v_mul_f32_e32 v6, v236, v6
	v_mul_f32_e32 v8, v237, v8
	v_cvt_pk_bf16_f32 v45, v6, v8
	s_nop 0
	s_nop 0
	s_nop 0
	s_nop 0
	v_mul_f32_e32 v6, v3, v35
	v_mul_f32_e32 v8, v3, v33
	s_waitcnt vmcnt(1)
	v_mul_f32_e32 v0, v0, v245
	s_waitcnt vmcnt(0)
	v_mul_f32_e32 v6, v6, v238
	v_mul_f32_e32 v8, v8, v239
	v_cvt_pk_bf16_f32 v46, v6, v8
	v_mul_f32_e32 v6, v3, v48
	v_mul_f32_e32 v6, v6, v240
	v_mul_f32_e32 v8, v3, v47
	v_mul_f32_e32 v8, v8, v241
	v_cvt_pk_bf16_f32 v47, v6, v8
	v_mul_f32_e32 v6, v3, v17
	v_mul_f32_e32 v6, v6, v242
	v_mul_f32_e32 v8, v3, v15
	v_mul_f32_e32 v8, v8, v243
	v_cvt_pk_bf16_f32 v48, v6, v8
	v_mul_f32_e32 v6, v3, v7
	v_mul_f32_e32 v6, v6, v244
	v_mad_i64_i32 v[14:15], s[6:7], v111, s84, v[94:95]
	v_cvt_pk_bf16_f32 v49, v6, v0
	global_load_dwordx4 v[2:5], v[14:15], off
	global_load_dwordx4 v[6:9], v[14:15], off offset:64
	s_waitcnt vmcnt(0) lgkmcnt(0)
	v_and_b32_e32 v19, 0xffff0000, v3
	v_and_b32_e32 v31, 0xffff0000, v7
	v_and_b32_e32 v30, 0xffff0000, v6
	v_lshlrev_b32_e32 v29, 16, v7
	v_lshlrev_b32_e32 v28, 16, v6
	v_pk_mul_f32 v[6:7], v[30:31], v[30:31]
	v_and_b32_e32 v35, 0xffff0000, v9
	v_and_b32_e32 v34, 0xffff0000, v8
	v_pk_fma_f32 v[6:7], v[28:29], v[28:29], v[6:7]
	v_lshlrev_b32_e32 v33, 16, v9
	v_lshlrev_b32_e32 v32, 16, v8
	v_pk_mul_f32 v[8:9], v[34:35], v[34:35]
	v_pk_add_f32 v[6:7], v[6:7], v[6:7] op_sel:[0,1] op_sel_hi:[1,0]
	v_pk_fma_f32 v[36:37], v[32:33], v[32:33], v[8:9]
	v_and_b32_e32 v55, 0xffff0000, v2
	v_pk_add_f32 v[50:51], v[36:37], v[6:7]
	global_load_dwordx4 v[6:9], v[14:15], off offset:128
	v_and_b32_e32 v54, 0xffff0000, v4
	global_load_dwordx4 v[14:17], v[14:15], off offset:192
	v_lshlrev_b32_e32 v18, 16, v3
	v_mul_f32_e32 v0, v19, v19
	v_lshlrev_b32_e32 v53, 16, v2
	v_lshlrev_b32_e32 v52, 16, v4
	v_pk_mul_f32 v[2:3], v[54:55], v[54:55]
	v_pk_fma_f32 v[20:21], v[18:19], v[18:19], v[0:1] op_sel_hi:[1,1,0]
	v_pk_fma_f32 v[2:3], v[52:53], v[52:53], v[2:3]
	v_lshlrev_b32_e32 v26, 16, v5
	v_and_b32_e32 v27, 0xffff0000, v5
	v_pk_add_f32 v[4:5], v[2:3], v[20:21] op_sel:[1,0] op_sel_hi:[0,1]
	v_pk_add_f32 v[2:3], v[2:3], v[4:5]
	s_waitcnt vmcnt(0) lgkmcnt(0)
	v_and_b32_e32 v59, 0xffff0000, v6
	v_lshlrev_b32_e32 v58, 16, v6
	v_lshlrev_b32_e32 v60, 16, v7
	v_and_b32_e32 v61, 0xffff0000, v7
	v_mad_i64_i32 v[6:7], s[6:7], v111, s84, v[106:107]
	v_mul_f32_e32 v0, v59, v59
	v_lshlrev_b32_e32 v70, 16, v15
	v_and_b32_e32 v71, 0xffff0000, v15
	global_load_dwordx2 v[66:67], v[6:7], off offset:256
	global_load_dwordx2 v[68:69], v[6:7], off offset:288
	v_pk_fma_f32 v[6:7], v[58:59], v[58:59], v[0:1] op_sel_hi:[1,1,0]
	v_mul_f32_e32 v0, v61, v61
	v_lshlrev_b32_e32 v15, 16, v17
	v_and_b32_e32 v72, 0xffff0000, v17
	v_mul_f32_e32 v56, v70, v70
	v_mul_f32_e32 v57, v71, v71
	v_lshlrev_b32_e32 v20, 16, v8
	v_and_b32_e32 v63, 0xffff0000, v14
	v_and_b32_e32 v62, 0xffff0000, v8
	v_pk_mov_b32 v[4:5], v[8:9], v[16:17] op_sel:[1,0]
	v_lshlrev_b32_e32 v17, 16, v16
	v_lshlrev_b32_e32 v16, 16, v9
	v_pk_fma_f32 v[8:9], v[60:61], v[60:61], v[0:1] op_sel_hi:[1,1,0]
	v_lshlrev_b32_e32 v21, 16, v14
	v_and_b32_e32 v65, 0xffff0000, v5
	v_and_b32_e32 v64, 0xffff0000, v4
	v_pk_mul_f32 v[4:5], v[62:63], v[62:63]
	v_mov_b32_e32 v7, v56
	v_mov_b32_e32 v9, v57
	v_pk_fma_f32 v[4:5], v[20:21], v[20:21], v[4:5]
	v_pk_add_f32 v[6:7], v[6:7], v[8:9]
	v_mul_f32_e32 v0, v27, v27
	v_pk_add_f32 v[4:5], v[4:5], v[6:7]
	v_pk_mul_f32 v[6:7], v[64:65], v[64:65]
	v_mov_b32_e32 v8, v2
	v_pk_fma_f32 v[6:7], v[16:17], v[16:17], v[6:7]
	v_mov_b32_e32 v9, v15
	v_pk_add_f32 v[4:5], v[6:7], v[4:5]
	v_pk_fma_f32 v[6:7], v[26:27], v[26:27], v[0:1] op_sel_hi:[1,1,0]
	v_mul_f32_e32 v73, v72, v72
	v_mov_b32_e32 v14, v6
	v_pk_add_f32 v[2:3], v[6:7], v[2:3]
	v_pk_mul_f32 v[6:7], v[14:15], v[8:9]
	s_movk_i32 s6, 0x5000
	v_mov_b32_e32 v3, v7
	v_pk_add_f32 v[6:7], v[36:37], v[50:51] op_sel:[1,0] op_sel_hi:[0,1]
	v_mov_b32_e32 v7, v73
	v_pk_add_f32 v[2:3], v[2:3], v[6:7]
	s_waitcnt vmcnt(0) lgkmcnt(0)
	v_and_b32_e32 v117, 0xffff0000, v67
	v_pk_add_f32 v[2:3], v[2:3], v[4:5]
	v_and_b32_e32 v116, 0xffff0000, v66
	v_add_f32_e32 v0, v2, v3
	ds_bpermute_b32 v2, v132, v0
	v_lshlrev_b32_e32 v115, 16, v67
	v_lshlrev_b32_e32 v114, 16, v66
	v_lshlrev_b32_e32 v108, 16, v69
	v_and_b32_e32 v110, 0xffff0000, v69
	s_waitcnt lgkmcnt(0)
	v_add_f32_e32 v0, v0, v2
	ds_bpermute_b32 v2, v133, v0
	v_lshlrev_b32_e32 v112, 16, v68
	v_and_b32_e32 v113, 0xffff0000, v68
	s_waitcnt lgkmcnt(0)
	v_add_f32_e32 v0, v0, v2
	v_fmamk_f32 v0, v0, 0x3c000000, v197
	v_cmp_gt_f32_e32 vcc, s47, v0
	v_mul_f32_e32 v2, 0x4b800000, v0
	s_nop 0
	v_cndmask_b32_e32 v0, v0, v2, vcc
	v_rsq_f32_e32 v0, v0
	s_nop 0
	v_mul_f32_e32 v2, 0x45800000, v0
	v_cndmask_b32_e32 v0, v0, v2, vcc
	s_nop 0
	s_nop 0
	s_nop 0
	s_nop 0
	v_mul_f32_e32 v14, v0, v53
	s_waitcnt vmcnt(0)
	v_mul_f32_e32 v6, v214, v14
	v_mul_f32_e32 v14, v0, v55
	v_mul_f32_e32 v7, v215, v14
	v_cvt_pk_bf16_f32 v50, v6, v7
	v_mul_f32_e32 v6, v0, v18
	v_mul_f32_e32 v6, v216, v6
	v_mul_f32_e32 v7, v0, v19
	v_mul_f32_e32 v7, v217, v7
	v_cvt_pk_bf16_f32 v51, v6, v7
	v_mul_f32_e32 v6, v0, v52
	v_mul_f32_e32 v2, v218, v6
	v_mul_f32_e32 v6, v0, v54
	v_mul_f32_e32 v3, v219, v6
	v_cvt_pk_bf16_f32 v52, v2, v3
	v_mul_f32_e32 v2, v0, v26
	v_mul_f32_e32 v3, v0, v27
	v_mul_f32_e32 v2, v220, v2
	v_mul_f32_e32 v3, v221, v3
	v_cvt_pk_bf16_f32 v53, v2, v3
	s_nop 0
	s_nop 0
	s_nop 0
	s_nop 0
	v_mul_f32_e32 v14, v0, v28
	s_waitcnt vmcnt(0)
; #define MFMA16(a, b, c) __builtin_amdgcn_mfma_f32_16x16x32_bf16((a), (b), (c), 0, 0, 0)
; __device__ __forceinline__ void kvproj_task(int t, int l, const float* kvnorm, const float* kgain, const bf16_t* P, const bf16_t* WUKV, bf16_t* KB, bf16_t* VT, int fr, int fq) {
;     ...
;     const bf16_t* wk0 = WUKV + ((size_t)l * 512 + h * 128 + fr) * 128 + fq * 8;
;     bf16x8 wf[2][4];
; #pragma unroll
;     for (int ks = 0; ks < 4; ++ks) wf[0][ks] = asfrag(ld8(wk0 + ks * 32));
;     f32x4 acc[2][8];
; #pragma unroll
;     for (int cb = 0; cb < 8; ++cb) { acc[0][cb] = (f32x4){0.f, 0.f, 0.f, 0.f}; acc[1][cb] = acc[0][cb];
;         const int nrow = cb < 7 ? (cb + 1) * 16 : 0;
; #pragma unroll
;         for (int ks = 0; ks < 4; ++ks) wf[(cb + 1) & 1][ks] = asfrag(ld8(wk0 + (size_t)nrow * 128 + ks * 32));
; #pragma unroll
;         for (int ks = 0; ks < 4; ++ks) { acc[0][cb] = MFMA16(wf[cb & 1][ks], bfr[0][ks], acc[0][cb]); acc[1][cb] = MFMA16(wf[cb & 1][ks], bfr[1][ks], acc[1][cb]); } }
	v_mul_f32_e32 v6, v222, v14
	v_mul_f32_e32 v14, v0, v30
	v_mul_f32_e32 v7, v223, v14
	v_cvt_pk_bf16_f32 v54, v6, v7
	v_mul_f32_e32 v6, v0, v29
	v_mul_f32_e32 v6, v224, v6
	v_mul_f32_e32 v7, v0, v31
	v_mul_f32_e32 v7, v225, v7
	v_cvt_pk_bf16_f32 v55, v6, v7
	v_mul_f32_e32 v6, v0, v32
	v_mul_f32_e32 v2, v226, v6
	v_mul_f32_e32 v6, v0, v34
	v_mul_f32_e32 v3, v227, v6
	v_cvt_pk_bf16_f32 v56, v2, v3
	v_mul_f32_e32 v2, v0, v33
	v_mul_f32_e32 v3, v0, v35
	v_mul_f32_e32 v2, v228, v2
	v_mul_f32_e32 v3, v229, v3
	v_cvt_pk_bf16_f32 v57, v2, v3
	s_nop 0
	s_nop 0
	s_nop 0
	s_nop 0
	v_mul_f32_e32 v14, v0, v58
	s_waitcnt vmcnt(0)
	v_mul_f32_e32 v6, v230, v14
	v_mul_f32_e32 v14, v0, v59
	v_mul_f32_e32 v7, v231, v14
	v_cvt_pk_bf16_f32 v58, v6, v7
	v_mul_f32_e32 v6, v0, v60
	v_mul_f32_e32 v6, v232, v6
	v_mul_f32_e32 v7, v0, v61
	v_mul_f32_e32 v7, v233, v7
	v_cvt_pk_bf16_f32 v59, v6, v7
	v_mul_f32_e32 v6, v0, v20
	v_mul_f32_e32 v2, v234, v6
	v_mul_f32_e32 v6, v0, v62
	v_mul_f32_e32 v3, v235, v6
	v_cvt_pk_bf16_f32 v60, v2, v3
	v_mul_f32_e32 v2, v0, v16
	v_mul_f32_e32 v3, v0, v64
	v_mul_f32_e32 v2, v236, v2
	v_mul_f32_e32 v3, v237, v3
	v_cvt_pk_bf16_f32 v61, v2, v3
	s_nop 0
	s_nop 0
	s_nop 0
	s_nop 0
	v_mul_f32_e32 v14, v0, v21
	s_waitcnt vmcnt(0)
	v_mul_f32_e32 v6, v14, v238
	v_mul_f32_e32 v14, v0, v63
	v_mul_f32_e32 v7, v14, v239
	v_cvt_pk_bf16_f32 v62, v6, v7
	v_mul_f32_e32 v6, v0, v70
	v_mul_f32_e32 v6, v6, v240
	v_mul_f32_e32 v7, v0, v71
	v_mul_f32_e32 v7, v7, v241
	v_cvt_pk_bf16_f32 v63, v6, v7
	v_mul_f32_e32 v6, v0, v17
	v_mul_f32_e32 v2, v6, v242
	v_mul_f32_e32 v6, v0, v65
	v_mul_f32_e32 v3, v6, v243
	v_cvt_pk_bf16_f32 v64, v2, v3
	v_mul_f32_e32 v2, v0, v15
	v_mul_f32_e32 v0, v0, v72
	v_mul_f32_e32 v0, v0, v245
	v_mul_f32_e32 v2, v2, v244
	v_cvt_pk_bf16_f32 v65, v2, v0
	v_lshl_or_b32 v0, s1, 14, v138
	v_pk_mul_f32 v[2:3], v[116:117], v[116:117]
	v_lshl_add_u64 v[148:149], v[0:1], 1, v[100:101]
	v_pk_fma_f32 v[118:119], v[114:115], v[114:115], v[2:3]
	global_load_dwordx4 v[2:5], v[148:149], off
	global_load_dwordx4 v[6:9], v[148:149], off offset:64
	global_load_dwordx4 v[14:17], v[148:149], off offset:128
	global_load_dwordx4 v[18:21], v[148:149], off offset:192
	v_add_co_u32_e32 v26, vcc, s21, v148
	v_add_u32_e32 v0, 0xffffc000, v109
	s_nop 0
	v_addc_co_u32_e32 v27, vcc, 0, v149, vcc
	global_load_dwordx4 v[30:33], v[26:27], off
	global_load_dwordx4 v[34:37], v[26:27], off offset:64
	global_load_dwordx4 v[66:69], v[26:27], off offset:128
	global_load_dwordx4 v[74:77], v[26:27], off offset:192
	s_waitcnt vmcnt(0) lgkmcnt(0)
	v_mfma_f32_16x16x32_bf16 v[26:29], v[2:5], v[22:25], 0
	v_mfma_f32_16x16x32_bf16 v[2:5], v[2:5], v[50:53], 0
	v_mfma_f32_16x16x32_bf16 v[26:29], v[6:9], v[38:41], v[26:29]
	v_mfma_f32_16x16x32_bf16 v[2:5], v[6:9], v[54:57], v[2:5]
	v_mfma_f32_16x16x32_bf16 v[6:9], v[14:17], v[42:45], v[26:29]
	v_mfma_f32_16x16x32_bf16 v[2:5], v[14:17], v[58:61], v[2:5]
	v_mfma_f32_16x16x32_bf16 v[70:73], v[18:21], v[46:49], v[6:9]
	v_mfma_f32_16x16x32_bf16 v[26:29], v[18:21], v[62:65], v[2:5]
	v_add_co_u32_e32 v18, vcc, s33, v148
	s_nop 5
	v_mov_b32_e32 v123, v71
	v_addc_co_u32_e32 v19, vcc, 0, v149, vcc
	global_load_dwordx4 v[2:5], v[18:19], off
	global_load_dwordx4 v[6:9], v[18:19], off offset:64
	global_load_dwordx4 v[14:17], v[18:19], off offset:128
	global_load_dwordx4 v[86:89], v[18:19], off offset:192
	v_mfma_f32_16x16x32_bf16 v[18:21], v[30:33], v[22:25], 0
	v_mov_b32_e32 v121, v70
	v_mfma_f32_16x16x32_bf16 v[30:33], v[30:33], v[50:53], 0
	v_mfma_f32_16x16x32_bf16 v[18:21], v[34:37], v[38:41], v[18:21]
	v_mfma_f32_16x16x32_bf16 v[30:33], v[34:37], v[54:57], v[30:33]
	v_mfma_f32_16x16x32_bf16 v[18:21], v[66:69], v[42:45], v[18:21]
	v_mfma_f32_16x16x32_bf16 v[30:33], v[66:69], v[58:61], v[30:33]
	v_mfma_f32_16x16x32_bf16 v[78:81], v[74:77], v[46:49], v[18:21]
	v_mfma_f32_16x16x32_bf16 v[18:21], v[74:77], v[62:65], v[30:33]
	v_add_co_u32_e32 v74, vcc, s22, v148
	s_nop 1
	v_addc_co_u32_e32 v75, vcc, 0, v149, vcc
	s_nop 1
	global_load_dwordx4 v[30:33], v[74:75], off
	global_load_dwordx4 v[34:37], v[74:75], off offset:64
	global_load_dwordx4 v[66:69], v[74:75], off offset:128
	s_nop 0
	global_load_dwordx4 v[74:77], v[74:75], off offset:192
	s_waitcnt vmcnt(0) lgkmcnt(0)
	v_mfma_f32_16x16x32_bf16 v[82:85], v[2:5], v[22:25], 0
	v_mfma_f32_16x16x32_bf16 v[2:5], v[2:5], v[50:53], 0
	v_mfma_f32_16x16x32_bf16 v[82:85], v[6:9], v[38:41], v[82:85]
	v_mfma_f32_16x16x32_bf16 v[2:5], v[6:9], v[54:57], v[2:5]
	v_mfma_f32_16x16x32_bf16 v[6:9], v[14:17], v[42:45], v[82:85]
	v_mfma_f32_16x16x32_bf16 v[2:5], v[14:17], v[58:61], v[2:5]
	v_mfma_f32_16x16x32_bf16 v[82:85], v[86:89], v[46:49], v[6:9]
	v_mfma_f32_16x16x32_bf16 v[14:17], v[86:89], v[62:65], v[2:5]
	v_add_co_u32_e32 v86, vcc, s0, v148
	s_nop 1
	v_addc_co_u32_e32 v87, vcc, 0, v149, vcc
	s_nop 1
	global_load_dwordx4 v[2:5], v[86:87], off
	global_load_dwordx4 v[6:9], v[86:87], off offset:64
	global_load_dwordx4 v[90:93], v[86:87], off offset:128
	global_load_dwordx4 v[140:143], v[86:87], off offset:192
	v_mfma_f32_16x16x32_bf16 v[86:89], v[30:33], v[22:25], 0
	v_mfma_f32_16x16x32_bf16 v[30:33], v[30:33], v[50:53], 0
	v_mfma_f32_16x16x32_bf16 v[86:89], v[34:37], v[38:41], v[86:89]
	v_mfma_f32_16x16x32_bf16 v[30:33], v[34:37], v[54:57], v[30:33]
	v_mfma_f32_16x16x32_bf16 v[34:37], v[66:69], v[42:45], v[86:89]
	v_mfma_f32_16x16x32_bf16 v[30:33], v[66:69], v[58:61], v[30:33]
	v_mfma_f32_16x16x32_bf16 v[86:89], v[74:77], v[46:49], v[34:37]
	v_mfma_f32_16x16x32_bf16 v[30:33], v[74:77], v[62:65], v[30:33]
	v_add_co_u32_e32 v74, vcc, s6, v148
	s_movk_i32 s6, 0x7000
	s_nop 0
	v_addc_co_u32_e32 v75, vcc, 0, v149, vcc
	s_nop 0
	global_load_dwordx4 v[34:37], v[74:75], off
	global_load_dwordx4 v[66:69], v[74:75], off offset:64
	global_load_dwordx4 v[144:147], v[74:75], off offset:128
	global_load_dwordx4 v[156:159], v[74:75], off offset:192
	s_waitcnt vmcnt(0) lgkmcnt(0)
; #define MFMA16(a, b, c) __builtin_amdgcn_mfma_f32_16x16x32_bf16((a), (b), (c), 0, 0, 0)
; __device__ __forceinline__ void kvproj_task(int t, int l, const float* kvnorm, const float* kgain, const bf16_t* P, const bf16_t* WUKV, bf16_t* KB, bf16_t* VT, int fr, int fq) {
;     ...
;     for (int cb = 0; cb < 8; ++cb) { acc[0][cb] = (f32x4){0.f, 0.f, 0.f, 0.f}; acc[1][cb] = acc[0][cb];
;         const int nrow = cb < 7 ? (cb + 1) * 16 : 0;
; #pragma unroll
;         for (int ks = 0; ks < 4; ++ks) wf[(cb + 1) & 1][ks] = asfrag(ld8(wk0 + (size_t)nrow * 128 + ks * 32));
; #pragma unroll
;         for (int ks = 0; ks < 4; ++ks) { acc[0][cb] = MFMA16(wf[cb & 1][ks], bfr[0][ks], acc[0][cb]); acc[1][cb] = MFMA16(wf[cb & 1][ks], bfr[1][ks], acc[1][cb]); } }
; #pragma unroll
;     for (int tb = 0; tb < 2; ++tb) { const int row = row0 + tb * 16, rr = isc ? row - ML : row;
;         const int b = isc ? rr >> 8 : rr >> 11, tpos = isc ? rr & 255 : rr & 2047, key = isc ? tpos : 256 + tpos;
;         float s2 = skr[tb];
; #pragma unroll
;         for (int cb = 0; cb < 4; ++cb) s2 += (acc[tb][cb][0] * acc[tb][cb][0] + acc[tb][cb][1] * acc[tb][cb][1]) + (acc[tb][cb][2] * acc[tb][cb][2] + acc[tb][cb][3] * acc[tb][cb][3]);
;         s2 += __shfl_xor(s2, 16); s2 += __shfl_xor(s2, 32);
;         const float rh = rsqrtf(s2 * (1.f / 96.f) + EPS);
	v_mfma_f32_16x16x32_bf16 v[74:77], v[2:5], v[22:25], 0
	v_mfma_f32_16x16x32_bf16 v[2:5], v[2:5], v[50:53], 0
	v_mfma_f32_16x16x32_bf16 v[74:77], v[6:9], v[38:41], v[74:77]
	v_mfma_f32_16x16x32_bf16 v[2:5], v[6:9], v[54:57], v[2:5]
	v_mfma_f32_16x16x32_bf16 v[6:9], v[90:93], v[42:45], v[74:77]
	v_mfma_f32_16x16x32_bf16 v[2:5], v[90:93], v[58:61], v[2:5]
	v_mfma_f32_16x16x32_bf16 v[74:77], v[140:143], v[46:49], v[6:9]
	v_mfma_f32_16x16x32_bf16 v[6:9], v[140:143], v[62:65], v[2:5]
	s_nop 5
	v_add_co_u32_e32 v2, vcc, s20, v148
	s_nop 1
	v_addc_co_u32_e32 v3, vcc, 0, v149, vcc
	global_load_dwordx4 v[90:93], v[2:3], off
	global_load_dwordx4 v[140:143], v[2:3], off offset:64
	global_load_dwordx4 v[160:163], v[2:3], off offset:128
	global_load_dwordx4 v[164:167], v[2:3], off offset:192
	v_mfma_f32_16x16x32_bf16 v[2:5], v[34:37], v[22:25], 0
	v_mfma_f32_16x16x32_bf16 v[34:37], v[34:37], v[50:53], 0
	v_mfma_f32_16x16x32_bf16 v[2:5], v[66:69], v[38:41], v[2:5]
	v_mfma_f32_16x16x32_bf16 v[34:37], v[66:69], v[54:57], v[34:37]
	v_mfma_f32_16x16x32_bf16 v[2:5], v[144:147], v[42:45], v[2:5]
	v_mfma_f32_16x16x32_bf16 v[34:37], v[144:147], v[58:61], v[34:37]
	v_mfma_f32_16x16x32_bf16 v[66:69], v[156:159], v[46:49], v[2:5]
	v_mfma_f32_16x16x32_bf16 v[2:5], v[156:159], v[62:65], v[34:37]
	s_nop 5
	v_add_co_u32_e32 v34, vcc, s6, v148
	s_nop 1
	v_addc_co_u32_e32 v35, vcc, 0, v149, vcc
	global_load_dwordx4 v[144:147], v[34:35], off
	global_load_dwordx4 v[156:159], v[34:35], off offset:64
	global_load_dwordx4 v[168:171], v[34:35], off offset:128
	global_load_dwordx4 v[172:175], v[34:35], off offset:192
	s_waitcnt vmcnt(0) lgkmcnt(0)
	v_mfma_f32_16x16x32_bf16 v[34:37], v[90:93], v[22:25], 0
	v_cmp_lt_i32_e32 vcc, s49, v109
	v_mfma_f32_16x16x32_bf16 v[22:25], v[144:147], v[22:25], 0
	v_mfma_f32_16x16x32_bf16 v[90:93], v[90:93], v[50:53], 0
	v_mfma_f32_16x16x32_bf16 v[50:53], v[144:147], v[50:53], 0
	v_mfma_f32_16x16x32_bf16 v[34:37], v[140:143], v[38:41], v[34:37]
	v_mfma_f32_16x16x32_bf16 v[22:25], v[156:159], v[38:41], v[22:25]
	v_mfma_f32_16x16x32_bf16 v[38:41], v[156:159], v[54:57], v[50:53]
	v_mfma_f32_16x16x32_bf16 v[90:93], v[140:143], v[54:57], v[90:93]
	v_cndmask_b32_e32 v54, v109, v0, vcc
	v_mul_f32_e32 v0, v72, v72
	s_nop 1
	v_mul_f32_e32 v50, v73, v73
	v_mfma_f32_16x16x32_bf16 v[34:37], v[160:163], v[42:45], v[34:37]
	v_mfma_f32_16x16x32_bf16 v[22:25], v[168:171], v[42:45], v[22:25]
	v_mfma_f32_16x16x32_bf16 v[42:45], v[168:171], v[58:61], v[38:41]
	v_mfma_f32_16x16x32_bf16 v[140:143], v[160:163], v[58:61], v[90:93]
	v_mfma_f32_16x16x32_bf16 v[90:93], v[164:167], v[46:49], v[34:37]
	v_mfma_f32_16x16x32_bf16 v[38:41], v[172:175], v[46:49], v[22:25]
	v_add_f32_e64 v46, v130, v131
	v_add_f32_e64 v47, v131, v130
	v_mov_b32_e32 v47, v0
	v_mul_f32_e32 v0, v125, v125
	v_pk_fma_f32 v[48:49], v[124:125], v[124:125], v[0:1] op_sel_hi:[1,1,0]
	v_mfma_f32_16x16x32_bf16 v[22:25], v[172:175], v[62:65], v[42:45]
	v_mov_b32_e32 v49, v50
	v_pk_add_f32 v[46:47], v[46:47], v[48:49]
	v_pk_mul_f32 v[48:49], v[78:79], v[78:79]
	v_pk_mul_f32 v[44:45], v[122:123], v[122:123]
	v_mul_f32_e32 v0, v86, v86
	v_pk_fma_f32 v[44:45], v[120:121], v[120:121], v[44:45]
	v_cndmask_b32_e32 v43, v200, v201, vcc
	v_pk_add_f32 v[44:45], v[44:45], v[46:47]
	v_pk_mul_f32 v[46:47], v[80:81], v[80:81]
	v_pk_add_f32 v[44:45], v[44:45], v[44:45] op_sel:[0,1] op_sel_hi:[1,0]
	v_pk_mov_b32 v[50:51], v[48:49], v[46:47] op_sel:[1,0]
	v_mov_b32_e32 v49, v47
	v_pk_add_f32 v[46:47], v[50:51], v[48:49]
	v_mul_f32_e32 v48, v87, v87
	v_pk_add_f32 v[46:47], v[46:47], v[46:47] op_sel:[0,1] op_sel_hi:[1,0]
	v_mov_b32_e32 v45, v0
	v_mov_b32_e32 v47, v48
	v_mul_f32_e32 v0, v83, v83
	v_mul_f32_e32 v49, v88, v88
	v_pk_add_f32 v[44:45], v[44:45], v[46:47]
	v_pk_fma_f32 v[46:47], v[82:83], v[82:83], v[0:1] op_sel_hi:[1,1,0]
	v_mul_f32_e32 v0, v85, v85
	v_mul_f32_e32 v50, v89, v89
	v_mov_b32_e32 v47, v49
	v_pk_fma_f32 v[48:49], v[84:85], v[84:85], v[0:1] op_sel_hi:[1,1,0]
	v_cndmask_b32_e64 v42, 11, 8, vcc
	v_mov_b32_e32 v49, v50
	v_pk_add_f32 v[46:47], v[46:47], v[48:49]
	v_and_b32_e32 v55, v54, v43
	v_pk_add_f32 v[44:45], v[44:45], v[46:47]
	v_add_u32_e32 v52, 0x100, v55
	v_add_f32_e32 v44, v44, v45
	ds_bpermute_b32 v46, v132, v44
	v_ashrrev_i32_e32 v45, v42, v54
	v_cndmask_b32_e32 v0, v52, v55, vcc
	v_lshl_or_b32 v50, v45, 2, s1
	v_lshrrev_b32_e32 v49, 6, v55
	s_waitcnt lgkmcnt(0)
	v_add_f32_e32 v44, v44, v46
	ds_bpermute_b32 v46, v133, v44
	v_mfma_f32_16x16x32_bf16 v[34:37], v[164:167], v[62:65], v[140:143]
	v_and_b32_e32 v64, 47, v54
	v_mov_b32_e32 v121, v122
	v_ashrrev_i32_e32 v51, 31, v50
	s_waitcnt lgkmcnt(0)
; __device__ __forceinline__ unsigned cvt_pk_bf16(float lo, float hi) { unsigned r; asm volatile("v_cvt_pk_bf16_f32 %0, %1, %2" : "=v"(r) : "v"(lo), "v"(hi)); return r; }
; __device__ __forceinline__ bf16_t tobf(float f) { return (bf16_t)(cvt_pk_bf16(f, 0.f) & 0xffffu); }
; __device__ __forceinline__ void kvproj_task(int t, int l, const float* kvnorm, const float* kgain, const bf16_t* P, const bf16_t* WUKV, bf16_t* KB, bf16_t* VT, int fr, int fq) {
;     ...
;         s2 += __shfl_xor(s2, 16); s2 += __shfl_xor(s2, 32);
;         const float rh = rsqrtf(s2 * (1.f / 96.f) + EPS);
;         bf16_t* kdst = KB + ((size_t)(b * 4 + h) * NKEY + key) * 96;
; #pragma unroll
;         for (int cb = 0; cb < 6; ++cb) { const f32x4 kg = *(const f32x4*)(kgain + l * 96 + cb * 16 + fq * 4); f32x4 v = (cb < 4 ? acc[tb][cb < 4 ? cb : 0] : kr[tb][cb >= 4 ? cb - 4 : 0]) * rh * kg;
;             if (cb >= 4) { const f32x4 rv = rope16(v, fq, (float)(cb == 4 ? (tpos >> 6) : (tpos & 63))); if (!isc) v = rv; }
;             u32x2 w; w.x = cvt_pk_bf16(v[0], v[1]); w.y = cvt_pk_bf16(v[2], v[3]);
;             *(u32x2*)(kdst + cb * 16 + fq * 4) = w; }
; #pragma unroll
;         for (int cb = 4; cb < 8; ++cb)
; #pragma unroll
;             for (int q = 0; q < 4; ++q) VT[((size_t)(b * 4 + h) * 64 + (cb - 4) * 16 + fq * 4 + q) * NKEY + key] = tobf(acc[tb][cb][q]); }
	v_add_f32_e32 v44, v44, v46
	v_fmamk_f32 v44, v44, 0x3c2aaaab, v197
	v_cmp_gt_f32_e64 s[38:39], s47, v44
	v_mul_f32_e32 v46, 0x4b800000, v44
	s_nop 0
	v_cndmask_b32_e64 v44, v44, v46, s[38:39]
	v_rsq_f32_e32 v44, v44
	s_nop 0
	v_mul_f32_e32 v46, 0x45800000, v44
	v_cndmask_b32_e64 v48, v44, v46, s[38:39]
	v_mad_i64_i32 v[44:45], s[6:7], v50, s9, v[0:1]
	v_mad_u64_u32 v[52:53], s[6:7], v44, s15, v[104:105]
	v_mad_i32_i24 v53, v45, s15, v53
	s_nop 0
	s_nop 0
	v_pk_mul_f32 v[56:57], v[70:71], v[48:49] op_sel_hi:[1,0]
	v_pk_mul_f32 v[54:55], v[72:73], v[48:49] op_sel_hi:[1,0]
	v_lshlrev_b32_e32 v0, 1, v0
	s_nop 0
	v_pk_mul_f32 v[44:45], v[246:247], v[56:57]
	v_pk_mul_f32 v[46:47], v[248:249], v[54:55]
	v_cvt_pk_bf16_f32 v44, v44, v45
	v_pk_mul_f32 v[56:57], v[78:79], v[48:49] op_sel_hi:[1,0]
	v_cvt_pk_bf16_f32 v45, v46, v47
	global_store_dwordx2 v[52:53], v[44:45], off
	s_nop 0
	s_nop 0
	v_pk_mul_f32 v[54:55], v[80:81], v[48:49] op_sel_hi:[1,0]
	s_nop 0
	v_pk_mul_f32 v[44:45], v[176:177], v[56:57]
	v_pk_mul_f32 v[46:47], v[178:179], v[54:55]
	v_cvt_pk_bf16_f32 v44, v44, v45
	v_pk_mul_f32 v[56:57], v[82:83], v[48:49] op_sel_hi:[1,0]
	v_cvt_pk_bf16_f32 v45, v46, v47
	global_store_dwordx2 v[52:53], v[44:45], off offset:32
	s_nop 0
	s_nop 0
	v_pk_mul_f32 v[54:55], v[84:85], v[48:49] op_sel_hi:[1,0]
	s_nop 0
	v_pk_mul_f32 v[44:45], v[180:181], v[56:57]
	v_pk_mul_f32 v[46:47], v[182:183], v[54:55]
	v_cvt_pk_bf16_f32 v44, v44, v45
	v_pk_mul_f32 v[56:57], v[86:87], v[48:49] op_sel_hi:[1,0]
	v_cvt_pk_bf16_f32 v45, v46, v47
	global_store_dwordx2 v[52:53], v[44:45], off offset:64
	s_nop 0
	s_nop 0
	v_pk_mul_f32 v[54:55], v[88:89], v[48:49] op_sel_hi:[1,0]
	s_nop 0
	v_pk_mul_f32 v[44:45], v[56:57], v[184:185]
	v_pk_mul_f32 v[46:47], v[54:55], v[186:187]
	v_cvt_pk_bf16_f32 v44, v44, v45
	v_mov_b32_e32 v54, v126
	v_cvt_pk_bf16_f32 v45, v46, v47
	global_store_dwordx2 v[52:53], v[44:45], off offset:96
	s_nop 0
	s_nop 0
	v_mov_b32_e32 v55, v128
	v_mov_b32_e32 v128, v127
	v_pk_mul_f32 v[54:55], v[48:49], v[54:55] op_sel_hi:[0,1]
	v_pk_mul_f32 v[56:57], v[48:49], v[128:129] op_sel_hi:[0,1]
	v_cvt_f32_ubyte0_e32 v49, v49
	v_mul_f32_e32 v58, v134, v49
	v_mul_f32_e32 v59, 0.15915494, v58
	v_cos_f32_e32 v58, v59
	v_sin_f32_e32 v60, v59
	v_mul_f32_e32 v59, v135, v49
	v_mul_f32_e32 v61, 0.15915494, v59
	v_cos_f32_e32 v59, v61
	v_sin_f32_e32 v61, v61
	s_nop 0
	v_pk_mul_f32 v[44:45], v[54:55], v[188:189]
	ds_bpermute_b32 v54, v133, v44
	ds_bpermute_b32 v55, v133, v45
	v_pk_mul_f32 v[46:47], v[56:57], v[190:191]
	ds_bpermute_b32 v56, v133, v46
	ds_bpermute_b32 v57, v133, v47
	s_waitcnt lgkmcnt(0)
	v_pk_mul_f32 v[54:55], v[60:61], v[54:55]
	v_mul_f32_e32 v60, v136, v49
	v_mul_f32_e32 v49, v137, v49
	v_mul_f32_e32 v61, 0.15915494, v60
	v_mul_f32_e32 v49, 0.15915494, v49
	v_sin_f32_e32 v62, v61
	v_sin_f32_e32 v63, v49
	v_cos_f32_e32 v60, v61
	v_cos_f32_e32 v61, v49
	v_cndmask_b32_e64 v55, v55, -v55, s[36:37]
	v_pk_mul_f32 v[56:57], v[62:63], v[56:57]
	v_cndmask_b32_e64 v54, v54, -v54, s[36:37]
	v_cndmask_b32_e64 v57, v57, -v57, s[36:37]
	v_cndmask_b32_e64 v56, v56, -v56, s[36:37]
	v_pk_fma_f32 v[54:55], v[58:59], v[44:45], v[54:55]
	v_pk_fma_f32 v[56:57], v[60:61], v[46:47], v[56:57]
	v_cndmask_b32_e32 v44, v54, v44, vcc
	v_cndmask_b32_e32 v45, v55, v45, vcc
	v_cndmask_b32_e32 v46, v56, v46, vcc
	v_cndmask_b32_e32 v47, v57, v47, vcc
	v_cvt_pk_bf16_f32 v44, v44, v45
	v_cvt_pk_bf16_f32 v45, v46, v47
	global_store_dwordx2 v[52:53], v[44:45], off offset:128
	global_load_dwordx4 v[44:47], v[102:103], off offset:320
	v_cvt_f32_ubyte0_e32 v61, v64
	v_mul_f32_e32 v56, v134, v61
	v_pk_mul_f32 v[54:55], v[48:49], v[124:125] op_sel_hi:[0,1]
	v_mul_f32_e32 v57, 0.15915494, v56
	v_pk_mul_f32 v[48:49], v[48:49], v[120:121] op_sel_hi:[0,1]
	v_cos_f32_e32 v56, v57
	v_sin_f32_e32 v58, v57
	v_mul_f32_e32 v57, v135, v61
	v_mul_f32_e32 v59, 0.15915494, v57
	v_cos_f32_e32 v57, v59
	v_sin_f32_e32 v59, v59
	s_waitcnt vmcnt(0)
	v_pk_mul_f32 v[44:45], v[54:55], v[44:45]
	v_pk_mul_f32 v[46:47], v[48:49], v[46:47]
	ds_bpermute_b32 v48, v133, v44
	ds_bpermute_b32 v49, v133, v45
	ds_bpermute_b32 v54, v133, v46
	ds_bpermute_b32 v55, v133, v47
	s_waitcnt lgkmcnt(0)
	v_pk_mul_f32 v[48:49], v[58:59], v[48:49]
	v_mul_f32_e32 v58, v136, v61
	v_mul_f32_e32 v59, 0.15915494, v58
	v_cos_f32_e32 v58, v59
	v_sin_f32_e32 v60, v59
	v_mul_f32_e32 v59, v137, v61
	v_mul_f32_e32 v61, 0.15915494, v59
	v_cos_f32_e32 v59, v61
	v_sin_f32_e32 v61, v61
	v_cndmask_b32_e64 v49, v49, -v49, s[36:37]
	v_cndmask_b32_e64 v48, v48, -v48, s[36:37]
	v_pk_fma_f32 v[48:49], v[56:57], v[44:45], v[48:49]
	v_pk_mul_f32 v[54:55], v[60:61], v[54:55]
	v_cndmask_b32_e32 v44, v48, v44, vcc
	v_cndmask_b32_e64 v55, v55, -v55, s[36:37]
	v_cndmask_b32_e64 v54, v54, -v54, s[36:37]
	v_pk_fma_f32 v[54:55], v[58:59], v[46:47], v[54:55]
	v_cndmask_b32_e32 v45, v49, v45, vcc
	v_cndmask_b32_e32 v46, v54, v46, vcc
	v_cndmask_b32_e32 v47, v55, v47, vcc
	v_cvt_pk_bf16_f32 v44, v44, v45
	v_cvt_pk_bf16_f32 v45, v46, v47
	v_lshlrev_b64 v[46:47], 6, v[50:51]
	global_store_dwordx2 v[52:53], v[44:45], off offset:160
	v_lshl_add_u64 v[44:45], s[40:41], 0, v[0:1]
	v_or_b32_e32 v0, v46, v96
	v_mad_u64_u32 v[44:45], s[6:7], v0, s88, v[44:45]
	v_cvt_pk_bf16_f32 v46, v74, v1
	v_mad_i32_i24 v45, v47, s88, v45
	global_store_short v[44:45], v46, off
	v_add_co_u32_e64 v46, s[38:39], s21, v44
	v_cvt_pk_bf16_f32 v0, v75, v1
	s_nop 1
	v_addc_co_u32_e64 v47, s[38:39], 0, v45, s[38:39]
	global_store_short v[46:47], v0, off offset:512
	v_add_co_u32_e64 v46, s[38:39], s33, v44
	v_cvt_pk_bf16_f32 v0, v76, v1
	s_nop 1
	v_addc_co_u32_e64 v47, s[38:39], 0, v45, s[38:39]
; __device__ __forceinline__ unsigned cvt_pk_bf16(float lo, float hi) { unsigned r; asm volatile("v_cvt_pk_bf16_f32 %0, %1, %2" : "=v"(r) : "v"(lo), "v"(hi)); return r; }
; __device__ __forceinline__ bf16_t tobf(float f) { return (bf16_t)(cvt_pk_bf16(f, 0.f) & 0xffffu); }
; __device__ __forceinline__ void kvproj_task(int t, int l, const float* kvnorm, const float* kgain, const bf16_t* P, const bf16_t* WUKV, bf16_t* KB, bf16_t* VT, int fr, int fq) {
;     ...
;     for (int tb = 0; tb < 2; ++tb) { const int row = row0 + tb * 16, rr = isc ? row - ML : row;
;         const int b = isc ? rr >> 8 : rr >> 11, tpos = isc ? rr & 255 : rr & 2047, key = isc ? tpos : 256 + tpos;
;         float s2 = skr[tb];
; #pragma unroll
;         for (int cb = 0; cb < 4; ++cb) s2 += (acc[tb][cb][0] * acc[tb][cb][0] + acc[tb][cb][1] * acc[tb][cb][1]) + (acc[tb][cb][2] * acc[tb][cb][2] + acc[tb][cb][3] * acc[tb][cb][3]);
;         s2 += __shfl_xor(s2, 16); s2 += __shfl_xor(s2, 32);
;         const float rh = rsqrtf(s2 * (1.f / 96.f) + EPS);
;         bf16_t* kdst = KB + ((size_t)(b * 4 + h) * NKEY + key) * 96;
; #pragma unroll
;         for (int cb = 0; cb < 6; ++cb) { const f32x4 kg = *(const f32x4*)(kgain + l * 96 + cb * 16 + fq * 4); f32x4 v = (cb < 4 ? acc[tb][cb < 4 ? cb : 0] : kr[tb][cb >= 4 ? cb - 4 : 0]) * rh * kg;
;             if (cb >= 4) { const f32x4 rv = rope16(v, fq, (float)(cb == 4 ? (tpos >> 6) : (tpos & 63))); if (!isc) v = rv; }
;             u32x2 w; w.x = cvt_pk_bf16(v[0], v[1]); w.y = cvt_pk_bf16(v[2], v[3]);
;             *(u32x2*)(kdst + cb * 16 + fq * 4) = w; }
; #pragma unroll
;         for (int cb = 4; cb < 8; ++cb)
; #pragma unroll
;             for (int q = 0; q < 4; ++q) VT[((size_t)(b * 4 + h) * 64 + (cb - 4) * 16 + fq * 4 + q) * NKEY + key] = tobf(acc[tb][cb][q]); }
	global_store_short v[46:47], v0, off offset:1024
	v_add_co_u32_e64 v46, s[38:39], s22, v44
	v_cvt_pk_bf16_f32 v0, v77, v1
	s_nop 1
	v_addc_co_u32_e64 v47, s[38:39], 0, v45, s[38:39]
	global_store_short v[46:47], v0, off offset:1536
	v_add_co_u32_e64 v46, s[38:39], s18, v44
	v_cvt_pk_bf16_f32 v0, v66, v1
	s_nop 1
	v_addc_co_u32_e64 v47, s[38:39], 0, v45, s[38:39]
	global_store_short v[46:47], v0, off
	v_add_co_u32_e64 v46, s[38:39], s23, v44
	v_cvt_pk_bf16_f32 v0, v67, v1
	s_nop 1
	v_addc_co_u32_e64 v47, s[38:39], 0, v45, s[38:39]
	global_store_short v[46:47], v0, off offset:512
	v_add_co_u32_e64 v46, s[38:39], s19, v44
	v_cvt_pk_bf16_f32 v0, v68, v1
	s_nop 1
	v_addc_co_u32_e64 v47, s[38:39], 0, v45, s[38:39]
	global_store_short v[46:47], v0, off offset:1024
	v_add_co_u32_e64 v46, s[38:39], s24, v44
	v_cvt_pk_bf16_f32 v0, v69, v1
	s_nop 1
	v_addc_co_u32_e64 v47, s[38:39], 0, v45, s[38:39]
	global_store_short v[46:47], v0, off offset:1536
	v_add_co_u32_e64 v46, s[38:39], s25, v44
	v_cvt_pk_bf16_f32 v0, v90, v1
	s_nop 1
	v_addc_co_u32_e64 v47, s[38:39], 0, v45, s[38:39]
	global_store_short v[46:47], v0, off
	v_add_co_u32_e64 v46, s[38:39], s26, v44
	v_cvt_pk_bf16_f32 v0, v91, v1
	s_nop 1
	v_addc_co_u32_e64 v47, s[38:39], 0, v45, s[38:39]
	global_store_short v[46:47], v0, off offset:512
	v_add_co_u32_e64 v46, s[38:39], s27, v44
	v_cvt_pk_bf16_f32 v0, v92, v1
	s_nop 1
	v_addc_co_u32_e64 v47, s[38:39], 0, v45, s[38:39]
	global_store_short v[46:47], v0, off offset:1024
	v_add_co_u32_e64 v46, s[38:39], s42, v44
	v_cvt_pk_bf16_f32 v0, v93, v1
	s_nop 1
	v_addc_co_u32_e64 v47, s[38:39], 0, v45, s[38:39]
	global_store_short v[46:47], v0, off offset:1536
	v_add_co_u32_e64 v46, s[38:39], s43, v44
	v_cvt_pk_bf16_f32 v0, v38, v1
	s_nop 1
	v_addc_co_u32_e64 v47, s[38:39], 0, v45, s[38:39]
	v_add_co_u32_e64 v38, s[38:39], s44, v44
	global_store_short v[46:47], v0, off
	v_cvt_pk_bf16_f32 v0, v39, v1
	s_nop 0
	v_addc_co_u32_e64 v39, s[38:39], 0, v45, s[38:39]
	global_store_short v[38:39], v0, off offset:512
	v_add_co_u32_e64 v38, s[38:39], s45, v44
	v_cvt_pk_bf16_f32 v0, v40, v1
	v_mul_f32_e32 v47, v32, v32
	s_nop 0
	v_addc_co_u32_e64 v39, s[38:39], 0, v45, s[38:39]
	global_store_short v[38:39], v0, off offset:1024
	v_add_co_u32_e64 v38, s[38:39], s46, v44
	v_cvt_pk_bf16_f32 v0, v41, v1
	s_nop 1
	v_addc_co_u32_e64 v39, s[38:39], 0, v45, s[38:39]
	global_store_short v[38:39], v0, off offset:1536
	v_add_u32_e32 v0, 0xffffc010, v109
	v_cndmask_b32_e32 v39, v111, v0, vcc
	v_mul_f32_e32 v0, v28, v28
	v_pk_add_f32 v[44:45], v[118:119], v[118:119] op_sel:[0,1] op_sel_hi:[1,0]
	v_and_b32_e32 v46, v39, v43
	v_mov_b32_e32 v45, v0
	v_mul_f32_e32 v0, v113, v113
	v_mul_f32_e32 v43, v29, v29
	v_mov_b32_e32 v111, v27
	v_pk_fma_f32 v[48:49], v[112:113], v[112:113], v[0:1] op_sel_hi:[1,1,0]
	v_mov_b32_e32 v109, v26
	v_pk_mul_f32 v[40:41], v[110:111], v[110:111]
	v_mov_b32_e32 v49, v43
	v_pk_fma_f32 v[40:41], v[108:109], v[108:109], v[40:41]
	v_pk_add_f32 v[44:45], v[44:45], v[48:49]
	v_pk_mul_f32 v[48:49], v[18:19], v[18:19]
	v_pk_add_f32 v[40:41], v[40:41], v[44:45]
	v_pk_mul_f32 v[44:45], v[20:21], v[20:21]
	v_mul_f32_e32 v0, v30, v30
	v_pk_mov_b32 v[50:51], v[48:49], v[44:45] op_sel:[1,0]
	v_mov_b32_e32 v49, v45
	v_pk_add_f32 v[44:45], v[50:51], v[48:49]
	v_mul_f32_e32 v43, v31, v31
	v_pk_add_f32 v[40:41], v[40:41], v[40:41] op_sel:[0,1] op_sel_hi:[1,0]
	v_pk_add_f32 v[44:45], v[44:45], v[44:45] op_sel:[0,1] op_sel_hi:[1,0]
	v_mov_b32_e32 v41, v0
	v_mov_b32_e32 v45, v43
	v_mul_f32_e32 v0, v15, v15
	v_pk_add_f32 v[40:41], v[40:41], v[44:45]
	v_pk_fma_f32 v[44:45], v[14:15], v[14:15], v[0:1] op_sel_hi:[1,1,0]
	v_mul_f32_e32 v0, v17, v17
	v_mul_f32_e32 v50, v33, v33
	v_pk_fma_f32 v[48:49], v[16:17], v[16:17], v[0:1] op_sel_hi:[1,1,0]
	v_mov_b32_e32 v45, v47
	v_mov_b32_e32 v49, v50
	v_pk_add_f32 v[44:45], v[44:45], v[48:49]
	v_add_u32_e32 v38, 0x100, v46
	v_pk_add_f32 v[40:41], v[40:41], v[44:45]
	v_cndmask_b32_e32 v0, v38, v46, vcc
	v_add_f32_e32 v40, v40, v41
	ds_bpermute_b32 v38, v132, v40
	v_ashrrev_i32_e32 v41, v42, v39
	v_mov_b32_e32 v109, v110
	s_waitcnt lgkmcnt(0)
	v_add_f32_e32 v38, v40, v38
	ds_bpermute_b32 v40, v133, v38
	s_waitcnt lgkmcnt(0)
	v_add_f32_e32 v38, v38, v40
	v_fmamk_f32 v38, v38, 0x3c2aaaab, v197
	v_cmp_gt_f32_e64 s[38:39], s47, v38
	v_mul_f32_e32 v40, 0x4b800000, v38
	s_nop 0
	v_cndmask_b32_e64 v38, v38, v40, s[38:39]
	v_rsq_f32_e32 v38, v38
	s_nop 0
	v_mul_f32_e32 v40, 0x45800000, v38
	v_cndmask_b32_e64 v38, v38, v40, s[38:39]
	v_lshl_or_b32 v40, v41, 2, s1
	v_mad_i64_i32 v[42:43], s[6:7], v40, s9, v[0:1]
	v_mad_u64_u32 v[44:45], s[6:7], v42, s15, v[104:105]
	v_lshrrev_b32_e32 v42, 6, v46
	s_nop 0
	s_nop 0
	v_pk_mul_f32 v[26:27], v[26:27], v[38:39] op_sel_hi:[1,0]
	v_mad_i32_i24 v45, v43, s15, v45
	v_pk_mul_f32 v[28:29], v[28:29], v[38:39] op_sel_hi:[1,0]
	v_pk_mul_f32 v[18:19], v[18:19], v[38:39] op_sel_hi:[1,0]
	v_pk_mul_f32 v[20:21], v[20:21], v[38:39] op_sel_hi:[1,0]
	v_pk_mul_f32 v[14:15], v[14:15], v[38:39] op_sel_hi:[1,0]
	v_pk_mul_f32 v[16:17], v[16:17], v[38:39] op_sel_hi:[1,0]
	v_ashrrev_i32_e32 v41, 31, v40
	v_lshlrev_b32_e32 v0, 1, v0
	s_mul_i32 s1, s74, 56
	s_add_i32 s5, s5, s1
	s_cmpk_gt_i32 s4, 0x8ff
	s_nop 0
	v_pk_mul_f32 v[26:27], v[246:247], v[26:27]
	v_pk_mul_f32 v[28:29], v[248:249], v[28:29]
	v_cvt_pk_bf16_f32 v26, v26, v27
	s_nop 0
	v_cvt_pk_bf16_f32 v27, v28, v29
	global_store_dwordx2 v[44:45], v[26:27], off
	s_nop 0
	s_nop 0
	s_nop 0
	v_pk_mul_f32 v[18:19], v[176:177], v[18:19]
	v_pk_mul_f32 v[20:21], v[178:179], v[20:21]
	v_cvt_pk_bf16_f32 v18, v18, v19
	s_nop 0
	v_cvt_pk_bf16_f32 v19, v20, v21
	global_store_dwordx2 v[44:45], v[18:19], off offset:32
	s_nop 0
	s_nop 0
	s_nop 0
	v_pk_mul_f32 v[14:15], v[180:181], v[14:15]
	v_pk_mul_f32 v[16:17], v[182:183], v[16:17]
	v_cvt_pk_bf16_f32 v14, v14, v15
	v_pk_mul_f32 v[20:21], v[30:31], v[38:39] op_sel_hi:[1,0]
	v_cvt_pk_bf16_f32 v15, v16, v17
	global_store_dwordx2 v[44:45], v[14:15], off offset:64
	s_nop 0
	s_nop 0
	v_pk_mul_f32 v[18:19], v[32:33], v[38:39] op_sel_hi:[1,0]
	v_cvt_f32_ubyte0_e32 v31, v42
	v_mul_f32_e32 v26, v134, v31
	v_mul_f32_e32 v27, 0.15915494, v26
	v_cos_f32_e32 v26, v27
	v_sin_f32_e32 v28, v27
	v_mul_f32_e32 v27, v135, v31
	v_mul_f32_e32 v29, 0.15915494, v27
	v_cos_f32_e32 v27, v29
	v_sin_f32_e32 v29, v29
	s_nop 0
	v_pk_mul_f32 v[14:15], v[20:21], v[184:185]
	v_pk_mul_f32 v[16:17], v[18:19], v[186:187]
	v_cvt_pk_bf16_f32 v14, v14, v15
	v_mov_b32_e32 v18, v114
	v_cvt_pk_bf16_f32 v15, v16, v17
	global_store_dwordx2 v[44:45], v[14:15], off offset:96
	s_nop 0
	s_nop 0
	v_mov_b32_e32 v19, v116
	v_pk_mul_f32 v[18:19], v[38:39], v[18:19] op_sel_hi:[0,1]
	v_mov_b32_e32 v116, v115
	v_pk_mul_f32 v[20:21], v[38:39], v[116:117] op_sel_hi:[0,1]
	s_nop 0
	v_pk_mul_f32 v[14:15], v[18:19], v[188:189]
	ds_bpermute_b32 v18, v133, v14
	ds_bpermute_b32 v19, v133, v15
	v_pk_mul_f32 v[16:17], v[20:21], v[190:191]
	ds_bpermute_b32 v20, v133, v16
	ds_bpermute_b32 v21, v133, v17
	s_waitcnt lgkmcnt(0)
; __device__ __forceinline__ unsigned cvt_pk_bf16(float lo, float hi) { unsigned r; asm volatile("v_cvt_pk_bf16_f32 %0, %1, %2" : "=v"(r) : "v"(lo), "v"(hi)); return r; }
; __device__ __forceinline__ bf16_t tobf(float f) { return (bf16_t)(cvt_pk_bf16(f, 0.f) & 0xffffu); }
; __device__ __forceinline__ void kvproj_task(int t, int l, const float* kvnorm, const float* kgain, const bf16_t* P, const bf16_t* WUKV, bf16_t* KB, bf16_t* VT, int fr, int fq) {
;     ...
;         for (int cb = 0; cb < 6; ++cb) { const f32x4 kg = *(const f32x4*)(kgain + l * 96 + cb * 16 + fq * 4); f32x4 v = (cb < 4 ? acc[tb][cb < 4 ? cb : 0] : kr[tb][cb >= 4 ? cb - 4 : 0]) * rh * kg;
;             if (cb >= 4) { const f32x4 rv = rope16(v, fq, (float)(cb == 4 ? (tpos >> 6) : (tpos & 63))); if (!isc) v = rv; }
;             u32x2 w; w.x = cvt_pk_bf16(v[0], v[1]); w.y = cvt_pk_bf16(v[2], v[3]);
;             *(u32x2*)(kdst + cb * 16 + fq * 4) = w; }
; #pragma unroll
;         for (int cb = 4; cb < 8; ++cb)
; #pragma unroll
;             for (int q = 0; q < 4; ++q) VT[((size_t)(b * 4 + h) * 64 + (cb - 4) * 16 + fq * 4 + q) * NKEY + key] = tobf(acc[tb][cb][q]); }
	v_pk_mul_f32 v[18:19], v[28:29], v[18:19]
	v_mul_f32_e32 v28, v136, v31
	v_mul_f32_e32 v29, 0.15915494, v28
	v_cos_f32_e32 v28, v29
	v_sin_f32_e32 v30, v29
	v_mul_f32_e32 v29, v137, v31
	v_mul_f32_e32 v31, 0.15915494, v29
	v_cos_f32_e32 v29, v31
	v_sin_f32_e32 v31, v31
	v_cndmask_b32_e64 v19, v19, -v19, s[36:37]
	v_cndmask_b32_e64 v18, v18, -v18, s[36:37]
	v_pk_fma_f32 v[18:19], v[26:27], v[14:15], v[18:19]
	v_pk_mul_f32 v[20:21], v[30:31], v[20:21]
	v_cndmask_b32_e32 v14, v18, v14, vcc
	v_cndmask_b32_e64 v21, v21, -v21, s[36:37]
	v_cndmask_b32_e64 v20, v20, -v20, s[36:37]
	v_pk_fma_f32 v[20:21], v[28:29], v[16:17], v[20:21]
	v_cndmask_b32_e32 v15, v19, v15, vcc
	v_cndmask_b32_e32 v16, v20, v16, vcc
	v_cndmask_b32_e32 v17, v21, v17, vcc
	v_cvt_pk_bf16_f32 v14, v14, v15
	v_cvt_pk_bf16_f32 v15, v16, v17
	global_store_dwordx2 v[44:45], v[14:15], off offset:128
	global_load_dwordx4 v[14:17], v[102:103], off offset:320
	v_and_b32_e32 v26, 63, v39
	v_cvt_f32_ubyte0_e32 v31, v26
	v_mul_f32_e32 v26, v134, v31
	v_pk_mul_f32 v[18:19], v[38:39], v[112:113] op_sel_hi:[0,1]
	v_mul_f32_e32 v27, 0.15915494, v26
	v_cos_f32_e32 v26, v27
	v_sin_f32_e32 v28, v27
	v_mul_f32_e32 v27, v135, v31
	v_mul_f32_e32 v29, 0.15915494, v27
	v_cos_f32_e32 v27, v29
	v_sin_f32_e32 v29, v29
	v_pk_mul_f32 v[20:21], v[38:39], v[108:109] op_sel_hi:[0,1]
	s_waitcnt vmcnt(0)
	v_pk_mul_f32 v[14:15], v[18:19], v[14:15]
	ds_bpermute_b32 v18, v133, v14
	ds_bpermute_b32 v19, v133, v15
	v_pk_mul_f32 v[16:17], v[20:21], v[16:17]
	ds_bpermute_b32 v20, v133, v16
	ds_bpermute_b32 v21, v133, v17
	s_waitcnt lgkmcnt(0)
	v_pk_mul_f32 v[18:19], v[28:29], v[18:19]
	v_mul_f32_e32 v28, v136, v31
	v_mul_f32_e32 v29, 0.15915494, v28
	v_cos_f32_e32 v28, v29
	v_sin_f32_e32 v30, v29
	v_mul_f32_e32 v29, v137, v31
	v_mul_f32_e32 v31, 0.15915494, v29
	v_cos_f32_e32 v29, v31
	v_sin_f32_e32 v31, v31
	v_cndmask_b32_e64 v19, v19, -v19, s[36:37]
	v_cndmask_b32_e64 v18, v18, -v18, s[36:37]
	v_pk_fma_f32 v[18:19], v[26:27], v[14:15], v[18:19]
	v_pk_mul_f32 v[20:21], v[30:31], v[20:21]
	v_cndmask_b32_e32 v14, v18, v14, vcc
	v_cndmask_b32_e64 v21, v21, -v21, s[36:37]
	v_cndmask_b32_e64 v20, v20, -v20, s[36:37]
	v_pk_fma_f32 v[20:21], v[28:29], v[16:17], v[20:21]
	v_cndmask_b32_e32 v15, v19, v15, vcc
	v_cndmask_b32_e32 v16, v20, v16, vcc
	v_cndmask_b32_e32 v17, v21, v17, vcc
	v_cvt_pk_bf16_f32 v14, v14, v15
	v_cvt_pk_bf16_f32 v15, v16, v17
	v_lshlrev_b64 v[16:17], 6, v[40:41]
	global_store_dwordx2 v[44:45], v[14:15], off offset:160
	v_lshl_add_u64 v[14:15], s[40:41], 0, v[0:1]
	v_or_b32_e32 v0, v16, v96
	v_mad_u64_u32 v[14:15], s[6:7], v0, s88, v[14:15]
	v_cvt_pk_bf16_f32 v6, v6, v1
	v_mad_i32_i24 v15, v17, s88, v15
	global_store_short v[14:15], v6, off
	v_add_co_u32_e32 v6, vcc, s21, v14
	v_cvt_pk_bf16_f32 v0, v7, v1
	s_nop 1
	v_addc_co_u32_e32 v7, vcc, 0, v15, vcc
	global_store_short v[6:7], v0, off offset:512
	v_add_co_u32_e32 v6, vcc, s33, v14
	v_cvt_pk_bf16_f32 v0, v8, v1
	s_nop 1
	v_addc_co_u32_e32 v7, vcc, 0, v15, vcc
	global_store_short v[6:7], v0, off offset:1024
	v_add_co_u32_e32 v6, vcc, s22, v14
	v_cvt_pk_bf16_f32 v0, v9, v1
	s_nop 1
	v_addc_co_u32_e32 v7, vcc, 0, v15, vcc
	global_store_short v[6:7], v0, off offset:1536
	v_add_co_u32_e32 v6, vcc, s18, v14
	v_cvt_pk_bf16_f32 v0, v2, v1
	s_nop 1
	v_addc_co_u32_e32 v7, vcc, 0, v15, vcc
	v_add_co_u32_e32 v2, vcc, s23, v14
	global_store_short v[6:7], v0, off
	v_cvt_pk_bf16_f32 v0, v3, v1
	s_nop 0
	v_addc_co_u32_e32 v3, vcc, 0, v15, vcc
	global_store_short v[2:3], v0, off offset:512
	v_add_co_u32_e32 v2, vcc, s19, v14
	v_cvt_pk_bf16_f32 v0, v4, v1
	s_nop 1
	v_addc_co_u32_e32 v3, vcc, 0, v15, vcc
	global_store_short v[2:3], v0, off offset:1024
	v_add_co_u32_e32 v2, vcc, s24, v14
	v_cvt_pk_bf16_f32 v0, v5, v1
	s_nop 1
	v_addc_co_u32_e32 v3, vcc, 0, v15, vcc
	global_store_short v[2:3], v0, off offset:1536
	v_add_co_u32_e32 v2, vcc, s25, v14
	v_cvt_pk_bf16_f32 v0, v34, v1
	s_nop 1
	v_addc_co_u32_e32 v3, vcc, 0, v15, vcc
	global_store_short v[2:3], v0, off
	v_add_co_u32_e32 v2, vcc, s26, v14
	v_cvt_pk_bf16_f32 v0, v35, v1
	s_nop 1
	v_addc_co_u32_e32 v3, vcc, 0, v15, vcc
	global_store_short v[2:3], v0, off offset:512
	v_add_co_u32_e32 v2, vcc, s27, v14
	v_cvt_pk_bf16_f32 v0, v36, v1
	s_nop 1
	v_addc_co_u32_e32 v3, vcc, 0, v15, vcc
	global_store_short v[2:3], v0, off offset:1024
	v_add_co_u32_e32 v2, vcc, s42, v14
	v_cvt_pk_bf16_f32 v0, v37, v1
	s_nop 1
	v_addc_co_u32_e32 v3, vcc, 0, v15, vcc
	global_store_short v[2:3], v0, off offset:1536
	v_add_co_u32_e32 v2, vcc, s43, v14
	v_cvt_pk_bf16_f32 v0, v22, v1
	s_nop 1
	v_addc_co_u32_e32 v3, vcc, 0, v15, vcc
	global_store_short v[2:3], v0, off
	v_add_co_u32_e32 v2, vcc, s44, v14
	v_cvt_pk_bf16_f32 v0, v23, v1
	s_nop 1
	v_addc_co_u32_e32 v3, vcc, 0, v15, vcc
	global_store_short v[2:3], v0, off offset:512
	v_add_co_u32_e32 v2, vcc, 0x38000, v14
	v_cvt_pk_bf16_f32 v0, v24, v1
	s_nop 1
	v_addc_co_u32_e32 v3, vcc, 0, v15, vcc
	global_store_short v[2:3], v0, off offset:1024
	v_add_co_u32_e32 v2, vcc, 0x39000, v14
	v_cvt_pk_bf16_f32 v0, v25, v1
	s_nop 1
	v_addc_co_u32_e32 v3, vcc, 0, v15, vcc
	global_store_short v[2:3], v0, off offset:1536
	s_cbranch_scc0 .LBB0_427
	s_movk_i32 s90, 0x1000
; #define LDX(tt) (((tt) >= 0 && (tt) < seqlen) ? bf1(xp[(size_t)(tt) * INP]) : 0.f)
; #define LDX(tt) (((tt) >= 0 && (tt) < seqlen) ? bf1(xp[(size_t)(tt) * INP]) : 0.f)
; template <bool PASS2> ...
;     const int fr = lane & 15, fq = lane >> 4;
;     const int blk = t & 3, c = (t >> 2) % NCH, b = (t >> 2) / NCH;
;     const int seqlen = c < 8 ? 256 : 2048, t0 = c < 8 ? c * 32 : (c - 8) * 32, rbase = c < 8 ? ML + b * 256 : b * 2048;
;     bf16x8 af[2][2];
;     if (!PASS2) {
;         const int ch = blk * 64 + lane;
;         const float w0 = convw[(l * 4 + 0) * 256 + ch], w1 = convw[(l * 4 + 1) * 256 + ch], w2 = convw[(l * 4 + 2) * 256 + ch], w3 = convw[(l * 4 + 3) * 256 + ch], cb = convb[l * 256 + ch];
;         const bf16_t* xp = P + (size_t)rbase * INP + OFF_LRU + ch;
;     ...
;         float xs[35];
; #pragma unroll
;         for (int s = 0; s < 35; ++s) xs[s] = LDX(t0 + s - 2);
.LBB0_429:
	s_mov_b64 s[40:41], s[72:73]
	v_mov_b32 v97, v194
	s_mov_b32 s33, 0x8000
	v_readfirstlane_b32 s24, v97
	s_ashr_i32 s1, s24, 6
	s_add_i32 s23, s1, s69
	s_lshl_b32 s1, s1, 14
	s_add_i32 s22, s1, 0
	s_cmpk_gt_i32 s23, 0x8ff
	v_and_b32_e32 v95, 63, v97
	s_cbranch_scc1 .LBB0_544
	s_ashr_i32 s36, s23, 2
	s_mul_hi_i32 s1, s36, 0x38e38e39
	s_lshr_b32 s4, s1, 31
	s_ashr_i32 s1, s1, 4
	s_add_i32 s1, s1, s4
	s_mul_i32 s4, s1, 0x48
	s_sub_i32 s4, s36, s4
	s_lshl_b32 s6, s4, 5
	s_lshl_b32 s5, s1, 8
	s_add_i32 s7, s6, 0xffffff00
	s_add_i32 s14, s5, 0x4000
	s_lshl_b32 s1, s1, 11
	s_cmp_lt_i32 s4, 8
	s_movk_i32 s4, 0x800
	s_cselect_b32 s5, 0x100, s4
	s_cselect_b32 s4, s6, s7
	s_cselect_b32 s1, s14, s1
	s_and_b32 s6, s24, 0xc0
	v_or_b32_e32 v9, s6, v95
	v_readlane_b32 s7, v254, 32
	v_readlane_b32 s44, v251, 24
	v_readlane_b32 s45, v251, 25
	v_or_b32_e32 v0, s7, v9
	v_readlane_b32 s46, v251, 26
	v_readlane_b32 s47, v251, 27
	v_readlane_b32 s48, v251, 28
	v_readlane_b32 s49, v251, 29
	v_readlane_b32 s50, v251, 30
	v_readlane_b32 s51, v251, 31
	v_readlane_b32 s52, v251, 32
	v_readlane_b32 s53, v251, 33
	v_readlane_b32 s54, v251, 34
	v_readlane_b32 s55, v251, 35
	v_readlane_b32 s56, v251, 36
	v_readlane_b32 s57, v251, 37
	v_readlane_b32 s58, v251, 38
	v_readlane_b32 s59, v251, 39
	v_readlane_b32 s14, v254, 21
	s_mul_hi_i32 s7, s1, 0x2200
	v_lshl_add_u64 v[2:3], v[0:1], 2, s[58:59]
	v_readlane_b32 s44, v251, 40
	global_load_dword v7, v[2:3], off
	global_load_dword v6, v[2:3], off offset:1024
	global_load_dword v5, v[2:3], off offset:2048
	global_load_dword v4, v[2:3], off offset:3072
	v_or_b32_e32 v0, s14, v9
	v_readlane_b32 s45, v251, 41
	s_mul_i32 s14, s1, 0x2200
	s_add_u32 s18, s40, s14
	v_lshl_add_u64 v[2:3], v[0:1], 2, s[44:45]
	global_load_dword v8, v[2:3], off
	s_addc_u32 s19, s41, s7
	v_lshlrev_b32_e32 v0, 1, v9
	s_cmp_lt_i32 s4, 2
	v_lshl_add_u64 v[2:3], s[18:19], 0, v[0:1]
	s_cselect_b64 s[18:19], -1, 0
	s_cmp_le_i32 s4, s5
	s_cselect_b64 s[20:21], -1, 0
	s_cmp_gt_i32 s4, s5
	v_readlane_b32 s15, v254, 22
	s_cselect_b64 s[26:27], -1, 0
	s_mov_b64 s[14:15], 0x8eb8340
	s_or_b64 s[18:19], s[18:19], s[26:27]
	v_lshl_add_u64 v[2:3], v[2:3], 0, s[14:15]
	v_mov_b32_e32 v0, 0
	s_and_b64 vcc, exec, s[18:19]
	v_mov_b32_e32 v9, 0
	v_readlane_b32 s46, v251, 42
	v_readlane_b32 s47, v251, 43
	v_readlane_b32 s48, v251, 44
	v_readlane_b32 s49, v251, 45
	v_readlane_b32 s50, v251, 46
	v_readlane_b32 s51, v251, 47
	v_readlane_b32 s52, v251, 48
	v_readlane_b32 s53, v251, 49
	v_readlane_b32 s54, v251, 50
	v_readlane_b32 s55, v251, 51
	v_readlane_b32 s56, v251, 52
	v_readlane_b32 s57, v251, 53
	v_readlane_b32 s58, v251, 54
	v_readlane_b32 s59, v251, 55
	s_cbranch_vccnz .LBB0_432
	s_add_i32 s7, s4, -2
	v_mad_u64_u32 v[14:15], s[18:19], s7, v202, v[2:3]
	global_load_ushort v9, v[14:15], off
	s_nop 0
	s_nop 0
.LBB0_432:
	s_cmp_lt_i32 s4, 1
	s_cselect_b64 s[18:19], -1, 0
	s_xor_b64 s[20:21], s[20:21], -1
	s_or_b64 s[18:19], s[18:19], s[20:21]
	s_and_b64 vcc, exec, s[18:19]
	s_cbranch_vccnz .LBB0_434
	s_add_i32 s7, s4, -1
	v_mad_u64_u32 v[14:15], s[18:19], s7, v202, v[2:3]
	global_load_ushort v0, v[14:15], off
	s_nop 0
	s_nop 0
.LBB0_434:
	v_mov_b32_e32 v14, 0
	s_cmp_ge_u32 s4, s5
	v_mov_b32_e32 v15, 0
	s_cbranch_scc1 .LBB0_436
	v_mad_u64_u32 v[16:17], s[18:19], s4, v202, v[2:3]
	global_load_ushort v15, v[16:17], off
	s_nop 0
	s_nop 0
.LBB0_436:
	s_or_b32 s7, s4, 1
	s_cmp_gt_i32 s4, -1
	s_cselect_b64 s[20:21], -1, 0
	s_cmp_lt_i32 s7, s5
	s_cselect_b64 s[18:19], -1, 0
	s_and_b64 s[18:19], s[20:21], s[18:19]
	s_andn2_b64 vcc, exec, s[18:19]
	s_cbranch_vccnz .LBB0_438
	v_mad_u64_u32 v[16:17], s[18:19], s7, v202, v[2:3]
	global_load_ushort v14, v[16:17], off
	s_nop 0
	s_nop 0
.LBB0_438:
	s_or_b32 s7, s4, 2
	s_cmp_lt_i32 s7, s5
	s_cselect_b64 s[18:19], -1, 0
	s_and_b64 s[18:19], s[20:21], s[18:19]
	v_mov_b32_e32 v16, 0
	s_andn2_b64 vcc, exec, s[18:19]
	v_mov_b32_e32 v17, 0
	s_cbranch_vccnz .LBB0_440
	v_mad_u64_u32 v[18:19], s[18:19], s7, v202, v[2:3]
	global_load_ushort v17, v[18:19], off
	s_nop 0
	s_nop 0
.LBB0_440:
	s_or_b32 s7, s4, 3
	s_cmp_lt_i32 s7, s5
	s_cselect_b64 s[18:19], -1, 0
	s_and_b64 s[18:19], s[20:21], s[18:19]
	s_andn2_b64 vcc, exec, s[18:19]
	s_cbranch_vccnz .LBB0_442
	v_mad_u64_u32 v[18:19], s[18:19], s7, v202, v[2:3]
	global_load_ushort v16, v[18:19], off
	s_nop 0
	s_nop 0
.LBB0_442:
	s_or_b32 s7, s4, 4
	s_cmp_lt_i32 s7, s5
	s_cselect_b64 s[18:19], -1, 0
	s_and_b64 s[18:19], s[20:21], s[18:19]
	v_mov_b32_e32 v18, 0
	s_andn2_b64 vcc, exec, s[18:19]
	v_mov_b32_e32 v19, 0
	s_cbranch_vccnz .LBB0_444
	v_mad_u64_u32 v[20:21], s[18:19], s7, v202, v[2:3]
	global_load_ushort v19, v[20:21], off
	s_nop 0
	s_nop 0
.LBB0_444:
	s_or_b32 s7, s4, 5
	s_cmp_lt_i32 s7, s5
	s_cselect_b64 s[18:19], -1, 0
	s_and_b64 s[18:19], s[20:21], s[18:19]
	s_andn2_b64 vcc, exec, s[18:19]
	s_cbranch_vccnz .LBB0_446
	v_mad_u64_u32 v[20:21], s[18:19], s7, v202, v[2:3]
	global_load_ushort v18, v[20:21], off
	s_nop 0
	s_nop 0
.LBB0_446:
	s_or_b32 s7, s4, 6
	s_cmp_lt_i32 s7, s5
	s_cselect_b64 s[18:19], -1, 0
	s_and_b64 s[18:19], s[20:21], s[18:19]
	v_mov_b32_e32 v20, 0
	s_andn2_b64 vcc, exec, s[18:19]
	v_mov_b32_e32 v21, 0
	s_cbranch_vccnz .LBB0_448
	v_mad_u64_u32 v[22:23], s[18:19], s7, v202, v[2:3]
	global_load_ushort v21, v[22:23], off
	s_nop 0
	s_nop 0
.LBB0_448:
	s_or_b32 s7, s4, 7
	s_cmp_lt_i32 s7, s5
	s_cselect_b64 s[18:19], -1, 0
	s_and_b64 s[18:19], s[20:21], s[18:19]
	s_andn2_b64 vcc, exec, s[18:19]
	s_cbranch_vccnz .LBB0_450
	v_mad_u64_u32 v[22:23], s[18:19], s7, v202, v[2:3]
	global_load_ushort v20, v[22:23], off
	s_nop 0
	s_nop 0
; #define LDX(tt) (((tt) >= 0 && (tt) < seqlen) ? bf1(xp[(size_t)(tt) * INP]) : 0.f)
; #define LDX(tt) (((tt) >= 0 && (tt) < seqlen) ? bf1(xp[(size_t)(tt) * INP]) : 0.f)
; template <bool PASS2> ...
;     ...
;         float xs[35];
; #pragma unroll
;         for (int s = 0; s < 35; ++s) xs[s] = LDX(t0 + s - 2);
.LBB0_450:
	s_or_b32 s7, s4, 8
	s_cmp_lt_i32 s7, s5
	s_cselect_b64 s[18:19], -1, 0
	s_and_b64 s[18:19], s[20:21], s[18:19]
	v_mov_b32_e32 v22, 0
	s_andn2_b64 vcc, exec, s[18:19]
	v_mov_b32_e32 v23, 0
	s_cbranch_vccnz .LBB0_452
	v_mad_u64_u32 v[24:25], s[18:19], s7, v202, v[2:3]
	global_load_ushort v23, v[24:25], off
	s_nop 0
	s_nop 0
.LBB0_452:
	s_or_b32 s7, s4, 9
	s_cmp_lt_i32 s7, s5
	s_cselect_b64 s[18:19], -1, 0
	s_and_b64 s[18:19], s[20:21], s[18:19]
	s_andn2_b64 vcc, exec, s[18:19]
	s_cbranch_vccnz .LBB0_454
	v_mad_u64_u32 v[24:25], s[18:19], s7, v202, v[2:3]
	global_load_ushort v22, v[24:25], off
	s_nop 0
	s_nop 0
.LBB0_454:
	s_or_b32 s7, s4, 10
	s_cmp_lt_i32 s7, s5
	s_cselect_b64 s[18:19], -1, 0
	s_and_b64 s[18:19], s[20:21], s[18:19]
	v_mov_b32_e32 v24, 0
	s_andn2_b64 vcc, exec, s[18:19]
	v_mov_b32_e32 v25, 0
	s_cbranch_vccnz .LBB0_456
	v_mad_u64_u32 v[26:27], s[18:19], s7, v202, v[2:3]
	global_load_ushort v25, v[26:27], off
	s_nop 0
	s_nop 0
.LBB0_456:
	s_or_b32 s7, s4, 11
	s_cmp_lt_i32 s7, s5
	s_cselect_b64 s[18:19], -1, 0
	s_and_b64 s[18:19], s[20:21], s[18:19]
	s_andn2_b64 vcc, exec, s[18:19]
	s_cbranch_vccnz .LBB0_458
	v_mad_u64_u32 v[26:27], s[18:19], s7, v202, v[2:3]
	global_load_ushort v24, v[26:27], off
	s_nop 0
	s_nop 0
.LBB0_458:
	s_or_b32 s7, s4, 12
	s_cmp_lt_i32 s7, s5
	s_cselect_b64 s[18:19], -1, 0
	s_and_b64 s[18:19], s[20:21], s[18:19]
	v_mov_b32_e32 v26, 0
	s_andn2_b64 vcc, exec, s[18:19]
	v_mov_b32_e32 v27, 0
	s_cbranch_vccnz .LBB0_460
	v_mad_u64_u32 v[28:29], s[18:19], s7, v202, v[2:3]
	global_load_ushort v27, v[28:29], off
	s_nop 0
	s_nop 0
.LBB0_460:
	s_or_b32 s7, s4, 13
	s_cmp_lt_i32 s7, s5
	s_cselect_b64 s[18:19], -1, 0
	s_and_b64 s[18:19], s[20:21], s[18:19]
	s_andn2_b64 vcc, exec, s[18:19]
	s_cbranch_vccnz .LBB0_462
	v_mad_u64_u32 v[28:29], s[18:19], s7, v202, v[2:3]
	global_load_ushort v26, v[28:29], off
	s_nop 0
	s_nop 0
.LBB0_462:
	s_or_b32 s7, s4, 14
	s_cmp_lt_i32 s7, s5
	s_cselect_b64 s[18:19], -1, 0
	s_and_b64 s[18:19], s[20:21], s[18:19]
	v_mov_b32_e32 v28, 0
	s_andn2_b64 vcc, exec, s[18:19]
	v_mov_b32_e32 v29, 0
	s_cbranch_vccnz .LBB0_464
	v_mad_u64_u32 v[30:31], s[18:19], s7, v202, v[2:3]
	global_load_ushort v29, v[30:31], off
	s_nop 0
	s_nop 0
.LBB0_464:
	s_or_b32 s7, s4, 15
	s_cmp_lt_i32 s7, s5
	s_cselect_b64 s[18:19], -1, 0
	s_and_b64 s[18:19], s[20:21], s[18:19]
	s_andn2_b64 vcc, exec, s[18:19]
	s_cbranch_vccnz .LBB0_466
	v_mad_u64_u32 v[30:31], s[18:19], s7, v202, v[2:3]
	global_load_ushort v28, v[30:31], off
	s_nop 0
	s_nop 0
.LBB0_466:
	s_or_b32 s7, s4, 16
	s_cmp_lt_i32 s7, s5
	s_cselect_b64 s[18:19], -1, 0
	s_and_b64 s[18:19], s[20:21], s[18:19]
	v_mov_b32_e32 v30, 0
	s_andn2_b64 vcc, exec, s[18:19]
	v_mov_b32_e32 v31, 0
	s_cbranch_vccnz .LBB0_468
	v_mad_u64_u32 v[32:33], s[18:19], s7, v202, v[2:3]
	global_load_ushort v31, v[32:33], off
	s_nop 0
	s_nop 0
.LBB0_468:
	s_or_b32 s7, s4, 17
	s_cmp_lt_i32 s7, s5
	s_cselect_b64 s[18:19], -1, 0
	s_and_b64 s[18:19], s[20:21], s[18:19]
	s_andn2_b64 vcc, exec, s[18:19]
	s_cbranch_vccnz .LBB0_470
	v_mad_u64_u32 v[32:33], s[18:19], s7, v202, v[2:3]
	global_load_ushort v30, v[32:33], off
	s_nop 0
	s_nop 0
.LBB0_470:
	s_or_b32 s7, s4, 18
	s_cmp_lt_i32 s7, s5
	s_cselect_b64 s[18:19], -1, 0
	s_and_b64 s[18:19], s[20:21], s[18:19]
	v_mov_b32_e32 v32, 0
	s_andn2_b64 vcc, exec, s[18:19]
	v_mov_b32_e32 v33, 0
	s_cbranch_vccnz .LBB0_472
	v_mad_u64_u32 v[34:35], s[18:19], s7, v202, v[2:3]
	global_load_ushort v33, v[34:35], off
	s_nop 0
	s_nop 0
.LBB0_472:
	s_or_b32 s7, s4, 19
	s_cmp_lt_i32 s7, s5
	s_cselect_b64 s[18:19], -1, 0
	s_and_b64 s[18:19], s[20:21], s[18:19]
	s_andn2_b64 vcc, exec, s[18:19]
	s_cbranch_vccnz .LBB0_474
	v_mad_u64_u32 v[34:35], s[18:19], s7, v202, v[2:3]
	global_load_ushort v32, v[34:35], off
	s_nop 0
	s_nop 0
.LBB0_474:
	s_or_b32 s7, s4, 20
	s_cmp_lt_i32 s7, s5
	s_cselect_b64 s[18:19], -1, 0
	s_and_b64 s[18:19], s[20:21], s[18:19]
	v_mov_b32_e32 v34, 0
	s_andn2_b64 vcc, exec, s[18:19]
	v_mov_b32_e32 v35, 0
	s_cbranch_vccnz .LBB0_476
	v_mad_u64_u32 v[36:37], s[18:19], s7, v202, v[2:3]
	global_load_ushort v35, v[36:37], off
	s_nop 0
	s_nop 0
.LBB0_476:
	s_or_b32 s7, s4, 21
	s_cmp_lt_i32 s7, s5
	s_cselect_b64 s[18:19], -1, 0
	s_and_b64 s[18:19], s[20:21], s[18:19]
	s_andn2_b64 vcc, exec, s[18:19]
	s_cbranch_vccnz .LBB0_478
	v_mad_u64_u32 v[36:37], s[18:19], s7, v202, v[2:3]
	global_load_ushort v34, v[36:37], off
	s_nop 0
	s_nop 0
.LBB0_478:
	s_or_b32 s7, s4, 22
	s_cmp_lt_i32 s7, s5
	s_cselect_b64 s[18:19], -1, 0
	s_and_b64 s[18:19], s[20:21], s[18:19]
	v_mov_b32_e32 v36, 0
	s_andn2_b64 vcc, exec, s[18:19]
	v_mov_b32_e32 v37, 0
	s_cbranch_vccnz .LBB0_480
	v_mad_u64_u32 v[38:39], s[18:19], s7, v202, v[2:3]
	global_load_ushort v37, v[38:39], off
	s_nop 0
	s_nop 0
; #define LDX(tt) (((tt) >= 0 && (tt) < seqlen) ? bf1(xp[(size_t)(tt) * INP]) : 0.f)
; #define LDX(tt) (((tt) >= 0 && (tt) < seqlen) ? bf1(xp[(size_t)(tt) * INP]) : 0.f)
; template <bool PASS2> ...
;     ...
;         float xs[35];
; #pragma unroll
;         for (int s = 0; s < 35; ++s) xs[s] = LDX(t0 + s - 2);
.LBB0_480:
	s_or_b32 s7, s4, 23
	s_cmp_lt_i32 s7, s5
	s_cselect_b64 s[18:19], -1, 0
	s_and_b64 s[18:19], s[20:21], s[18:19]
	s_andn2_b64 vcc, exec, s[18:19]
	s_cbranch_vccnz .LBB0_482
	v_mad_u64_u32 v[38:39], s[18:19], s7, v202, v[2:3]
	global_load_ushort v36, v[38:39], off
	s_nop 0
	s_nop 0
.LBB0_482:
	s_or_b32 s7, s4, 24
	s_cmp_lt_i32 s7, s5
	s_cselect_b64 s[18:19], -1, 0
	s_and_b64 s[18:19], s[20:21], s[18:19]
	v_mov_b32_e32 v38, 0
	s_andn2_b64 vcc, exec, s[18:19]
	v_mov_b32_e32 v39, 0
	s_cbranch_vccnz .LBB0_484
	v_mad_u64_u32 v[40:41], s[18:19], s7, v202, v[2:3]
	global_load_ushort v39, v[40:41], off
	s_nop 0
	s_nop 0
.LBB0_484:
	s_or_b32 s7, s4, 25
	s_cmp_lt_i32 s7, s5
	s_cselect_b64 s[18:19], -1, 0
	s_and_b64 s[18:19], s[20:21], s[18:19]
	s_andn2_b64 vcc, exec, s[18:19]
	s_cbranch_vccnz .LBB0_486
	v_mad_u64_u32 v[40:41], s[18:19], s7, v202, v[2:3]
	global_load_ushort v38, v[40:41], off
	s_nop 0
	s_nop 0
.LBB0_486:
	s_or_b32 s7, s4, 26
	s_cmp_lt_i32 s7, s5
	s_cselect_b64 s[18:19], -1, 0
	s_and_b64 s[18:19], s[20:21], s[18:19]
	v_mov_b32_e32 v40, 0
	s_andn2_b64 vcc, exec, s[18:19]
	v_mov_b32_e32 v41, 0
	s_cbranch_vccnz .LBB0_488
	v_mad_u64_u32 v[42:43], s[18:19], s7, v202, v[2:3]
	global_load_ushort v41, v[42:43], off
	s_nop 0
	s_nop 0
.LBB0_488:
	s_or_b32 s7, s4, 27
	s_cmp_lt_i32 s7, s5
	s_cselect_b64 s[18:19], -1, 0
	s_and_b64 s[18:19], s[20:21], s[18:19]
	s_andn2_b64 vcc, exec, s[18:19]
	s_cbranch_vccnz .LBB0_490
	v_mad_u64_u32 v[42:43], s[18:19], s7, v202, v[2:3]
	global_load_ushort v40, v[42:43], off
	s_nop 0
	s_nop 0
.LBB0_490:
	s_or_b32 s7, s4, 28
	s_cmp_lt_i32 s7, s5
	s_cselect_b64 s[18:19], -1, 0
	s_and_b64 s[18:19], s[20:21], s[18:19]
	v_mov_b32_e32 v42, 0
	s_andn2_b64 vcc, exec, s[18:19]
	v_mov_b32_e32 v43, 0
	s_cbranch_vccnz .LBB0_492
	v_mad_u64_u32 v[44:45], s[18:19], s7, v202, v[2:3]
	global_load_ushort v43, v[44:45], off
	s_nop 0
	s_nop 0
.LBB0_492:
	s_or_b32 s7, s4, 29
	s_cmp_lt_i32 s7, s5
	s_cselect_b64 s[18:19], -1, 0
	s_and_b64 s[18:19], s[20:21], s[18:19]
	s_andn2_b64 vcc, exec, s[18:19]
	s_cbranch_vccnz .LBB0_494
	v_mad_u64_u32 v[44:45], s[18:19], s7, v202, v[2:3]
	global_load_ushort v42, v[44:45], off
	s_nop 0
	s_nop 0
.LBB0_494:
	s_or_b32 s7, s4, 30
	s_cmpk_gt_i32 s4, 0xffe1
	s_cselect_b64 s[18:19], -1, 0
	s_cmp_lt_i32 s7, s5
	s_cselect_b64 s[20:21], -1, 0
	s_and_b64 s[18:19], s[18:19], s[20:21]
	v_mov_b32_e32 v44, 0
	s_andn2_b64 vcc, exec, s[18:19]
	v_mov_b32_e32 v45, 0
	s_cbranch_vccnz .LBB0_496
	v_mad_u64_u32 v[46:47], s[18:19], s7, v202, v[2:3]
	global_load_ushort v45, v[46:47], off
	s_nop 0
	s_nop 0
.LBB0_496:
	s_or_b32 s7, s4, 31
	s_cmpk_gt_i32 s4, 0xffe0
	s_cselect_b64 s[18:19], -1, 0
	s_cmp_lt_i32 s7, s5
	s_cselect_b64 s[20:21], -1, 0
	s_and_b64 s[18:19], s[18:19], s[20:21]
	s_andn2_b64 vcc, exec, s[18:19]
	s_cbranch_vccnz .LBB0_498
	v_mad_u64_u32 v[46:47], s[18:19], s7, v202, v[2:3]
	global_load_ushort v44, v[46:47], off
	s_nop 0
	s_nop 0
.LBB0_498:
	s_waitcnt vmcnt(0) lgkmcnt(0)
	v_lshlrev_b32_e32 v9, 16, v9
	v_lshlrev_b32_e32 v0, 16, v0
	v_lshlrev_b32_e32 v15, 16, v15
	v_lshlrev_b32_e32 v14, 16, v14
	v_lshlrev_b32_e32 v17, 16, v17
	v_lshlrev_b32_e32 v16, 16, v16
	v_lshlrev_b32_e32 v19, 16, v19
	v_lshlrev_b32_e32 v18, 16, v18
	v_lshlrev_b32_e32 v21, 16, v21
	v_lshlrev_b32_e32 v20, 16, v20
	v_lshlrev_b32_e32 v23, 16, v23
	v_lshlrev_b32_e32 v22, 16, v22
	v_lshlrev_b32_e32 v25, 16, v25
	v_lshlrev_b32_e32 v24, 16, v24
	v_lshlrev_b32_e32 v27, 16, v27
	v_lshlrev_b32_e32 v26, 16, v26
	v_lshlrev_b32_e32 v29, 16, v29
	v_lshlrev_b32_e32 v28, 16, v28
	v_lshlrev_b32_e32 v31, 16, v31
	v_lshlrev_b32_e32 v30, 16, v30
	v_lshlrev_b32_e32 v33, 16, v33
	v_lshlrev_b32_e32 v32, 16, v32
	v_lshlrev_b32_e32 v35, 16, v35
	v_lshlrev_b32_e32 v34, 16, v34
	v_lshlrev_b32_e32 v37, 16, v37
	v_lshlrev_b32_e32 v36, 16, v36
	v_lshlrev_b32_e32 v39, 16, v39
	v_lshlrev_b32_e32 v38, 16, v38
	v_lshlrev_b32_e32 v41, 16, v41
	v_lshlrev_b32_e32 v40, 16, v40
	v_lshlrev_b32_e32 v43, 16, v43
	v_lshlrev_b32_e32 v42, 16, v42
	v_lshlrev_b32_e32 v45, 16, v45
	v_lshlrev_b32_e32 v44, 16, v44
	s_nop 0
	s_nop 0
	s_nop 0
	s_nop 0
	s_nop 0
	s_nop 0
	s_nop 0
	s_nop 0
	s_nop 0
	s_nop 0
	s_nop 0
	s_nop 0
	s_nop 0
	s_add_i32 s7, s4, 32
	s_cmpk_gt_i32 s4, 0xffdf
	s_cselect_b64 s[18:19], -1, 0
	s_cmp_lt_i32 s7, s5
	s_cselect_b64 s[20:21], -1, 0
	s_and_b64 s[18:19], s[18:19], s[20:21]
	s_andn2_b64 vcc, exec, s[18:19]
	v_mov_b32_e32 v46, 0
	s_cbranch_vccnz .LBB0_500
	v_mad_u64_u32 v[2:3], s[18:19], s7, v202, v[2:3]
	global_load_ushort v2, v[2:3], off
	s_waitcnt vmcnt(0) lgkmcnt(0)
	v_lshlrev_b32_e32 v46, 16, v2

; #define MFMA16(a, b, c) __builtin_amdgcn_mfma_f32_16x16x32_bf16((a), (b), (c), 0, 0, 0)
; template <bool PASS2> ...
;     ...
;     for (int d = 0; d < 2; ++d) {
;         bf16x8 wfa[4][2], wfx[4][2]; float pba[4], pbx[4], plm[4], phin[4]; unsigned pkv[4][2][4];
;         unsigned* labd = LAB + ((size_t)d * MH + rbase + t0 + fq * 4) * 256 + blk * 64 + fr;
; #pragma unroll
;         for (int cb = 0; cb < 4; ++cb) {
;             const int chn = blk * 64 + cb * 16 + fr;
;             if (!PASS2) {
;                 const bf16_t* wa = WLRU + ((size_t)(((l * 2 + d) * 2 + 0) * 4 + blk) * 64 + cb * 16 + fr) * 64 + fq * 8;
; #pragma unroll
;                 for (int ks = 0; ks < 2; ++ks) { wfa[cb][ks] = asfrag(ld8(wa + ks * 32)); wfx[cb][ks] = asfrag(ld8(wa + 4 * 4096 + ks * 32)); }
;                 pba[cb] = b_a[(l * 2 + d) * 256 + chn]; pbx[cb] = b_x[(l * 2 + d) * 256 + chn]; plm[cb] = lam[(l * 2 + d) * 256 + chn];
;             } else {
;                 phin[cb] = LRH[((size_t)(b * NCH + c) * 2 + d) * 256 + chn];
; #pragma unroll
;                 for (int tb = 0; tb < 2; ++tb)
; #pragma unroll
;                     for (int q = 0; q < 4; ++q) pkv[cb][tb][q] = labd[(size_t)(tb * 16 + q) * 256 + cb * 16];
;             }
;         }
; #pragma unroll
;         for (int cb = 0; cb < 4; ++cb) {
;             const int chn = blk * 64 + cb * 16 + fr;
;             float av[2][4], bv[2][4], Ap[2], Bp[2];
;             if (!PASS2) {
;                 f32x4 ga[2], gx[2];
;                 ga[0] = ga[1] = gx[0] = gx[1] = (f32x4){0.f, 0.f, 0.f, 0.f};
; #pragma unroll
;                 for (int ks = 0; ks < 2; ++ks) {
; #pragma unroll
;                     for (int tb = 0; tb < 2; ++tb) { ga[tb] = MFMA16(af[tb][ks], wfa[cb][ks], ga[tb]); gx[tb] = MFMA16(af[tb][ks], wfx[cb][ks], gx[tb]); } }
;                 const float ba = pba[cb], bx = pbx[cb], sp = log1pf(__expf(-plm[cb]));
.LBB0_502:
	s_or_b32 s1, s4, s2
	s_waitcnt lgkmcnt(0)
	v_lshlrev_b32_e32 v0, 6, v90
	v_lshl_or_b32 v0, s1, 15, v0
	v_lshl_add_u64 v[26:27], v[0:1], 1, v[88:89]
	global_load_dwordx4 v[22:25], v[26:27], off
	global_load_dwordx4 v[66:69], v[26:27], off offset:64
	v_add_co_u32_e32 v118, vcc, s33, v26
	v_mov_b32_e32 v29, v1
	v_lshl_or_b32 v28, s1, 8, v90
	v_readlane_b32 s52, v251, 40
	v_addc_co_u32_e32 v119, vcc, 0, v27, vcc
	v_lshlrev_b64 v[28:29], 2, v[28:29]
	v_readlane_b32 s54, v251, 42
	v_readlane_b32 s55, v251, 43
	global_load_dwordx4 v[62:65], v[118:119], off
	v_readlane_b32 s58, v251, 46
	v_lshl_add_u64 v[120:121], s[54:55], 0, v[28:29]
	global_load_dword v122, v[120:121], off
	global_load_dwordx4 v[78:81], v[118:119], off offset:64
	v_readlane_b32 s59, v251, 47
	v_readlane_b32 s62, v251, 50
	v_readlane_b32 s63, v251, 51
	v_lshl_add_u64 v[74:75], s[58:59], 0, v[28:29]
	s_mov_b32 s1, 0x9000
	v_lshl_add_u64 v[76:77], s[62:63], 0, v[28:29]
	v_add_co_u32_e32 v28, vcc, s90, v26
	s_mul_i32 s88, s4, 0x4800
	s_nop 0
	v_addc_co_u32_e32 v29, vcc, 0, v27, vcc
	global_load_dwordx4 v[58:61], v[26:27], off offset:2048
	global_load_dwordx4 v[54:57], v[26:27], off offset:2112
	v_add_co_u32_e32 v26, vcc, s1, v26
	v_lshl_add_u64 v[30:31], v[98:99], 0, s[88:89]
	s_nop 0
	v_addc_co_u32_e32 v27, vcc, 0, v27, vcc
	v_lshlrev_b64 v[100:101], 10, v[30:31]
	global_load_dwordx4 v[46:49], v[28:29], off
	global_load_dwordx4 v[38:41], v[28:29], off offset:64
	global_load_dwordx4 v[50:53], v[26:27], off
	global_load_dwordx4 v[42:45], v[26:27], off offset:64
	v_lshl_add_u64 v[100:101], v[86:87], 0, v[100:101]
	s_xor_b64 s[50:51], s[48:49], -1
	s_mov_b64 s[20:21], -1
	v_readlane_b32 s53, v251, 41
	v_readlane_b32 s56, v251, 44
	v_readlane_b32 s57, v251, 45
	v_readlane_b32 s60, v251, 48
	v_readlane_b32 s61, v251, 49
	v_readlane_b32 s64, v251, 52
	v_readlane_b32 s65, v251, 53
	v_readlane_b32 s66, v251, 54
	v_readlane_b32 s67, v251, 55
	s_waitcnt vmcnt(0) lgkmcnt(0)
	v_mfma_f32_16x16x32_bf16 v[70:73], v[2:5], v[22:25], 0
	v_mfma_f32_16x16x32_bf16 v[82:85], v[14:17], v[22:25], 0
	global_load_dwordx4 v[30:33], v[28:29], off offset:2048
	global_load_dwordx4 v[22:25], v[28:29], off offset:2112
	global_load_dwordx4 v[34:37], v[26:27], off offset:2048
	s_nop 0
	global_load_dwordx4 v[26:29], v[26:27], off offset:2112
	s_nop 0
	global_load_dword v123, v[74:75], off
	global_load_dword v108, v[74:75], off offset:64
	global_load_dword v105, v[74:75], off offset:128
	global_load_dword v102, v[74:75], off offset:192
	global_load_dword v124, v[76:77], off
	global_load_dword v107, v[76:77], off offset:64
	global_load_dword v104, v[76:77], off offset:128
	global_load_dword v0, v[76:77], off offset:192
	v_mfma_f32_16x16x32_bf16 v[110:113], v[2:5], v[62:65], 0
	global_load_dword v109, v[120:121], off offset:64
	global_load_dword v106, v[120:121], off offset:128
	global_load_dword v103, v[120:121], off offset:192
	v_mfma_f32_16x16x32_bf16 v[114:117], v[14:17], v[62:65], 0
	v_mul_f32_e32 v62, 0xbfb8aa3b, v122
	v_exp_f32_e32 v120, v62
	v_mfma_f32_16x16x32_bf16 v[74:77], v[6:9], v[66:69], v[70:73]
	v_mfma_f32_16x16x32_bf16 v[70:73], v[18:21], v[66:69], v[82:85]
	global_load_dwordx4 v[66:69], v[118:119], off offset:2048
	global_load_dwordx4 v[62:65], v[118:119], off offset:2112
	s_waitcnt vmcnt(0)
	s_nop 3
	v_add_f32_e32 v74, v123, v74
	v_mfma_f32_16x16x32_bf16 v[82:85], v[6:9], v[78:81], v[110:113]
	v_mul_f32_e32 v74, 0xbfb8aa3b, v74
	v_exp_f32_e32 v74, v74
	v_add_f32_e32 v75, v123, v75
	v_add_f32_e32 v112, 1.0, v120
	v_add_f32_e32 v113, -1.0, v112
	v_frexp_mant_f32_e32 v118, v112
	v_cvt_f64_f32_e32 v[110:111], v112
	v_sub_f32_e32 v119, v113, v112
	v_frexp_exp_i32_f64_e32 v110, v[110:111]
	v_cmp_gt_f32_e32 vcc, s70, v118
	v_sub_f32_e32 v113, v120, v113
	v_add_f32_e32 v111, 1.0, v119
	v_subbrev_co_u32_e32 v110, vcc, 0, v110, vcc
	v_add_f32_e32 v111, v113, v111
	v_sub_u32_e32 v113, 0, v110
	v_ldexp_f32 v112, v112, v113
	v_ldexp_f32 v111, v111, v113
	v_add_f32_e32 v113, -1.0, v112
	v_add_f32_e32 v118, 1.0, v112
	v_add_f32_e32 v119, 1.0, v113
	v_add_f32_e32 v121, -1.0, v118
	v_sub_f32_e32 v119, v112, v119
	v_sub_f32_e32 v112, v112, v121
	v_add_f32_e32 v119, v111, v119
	v_add_f32_e32 v111, v111, v112
	v_add_f32_e32 v121, v118, v111
	v_rcp_f32_e32 v122, v121
	v_add_f32_e32 v112, v113, v119
	v_sub_f32_e32 v118, v121, v118
	v_sub_f32_e32 v113, v112, v113
	v_sub_f32_e32 v111, v111, v118
	v_mul_f32_e32 v118, v112, v122
	v_sub_f32_e32 v113, v119, v113
	v_mul_f32_e32 v119, v121, v118
	v_fma_f32 v125, v118, v121, -v119
	v_fmac_f32_e32 v125, v118, v111
	v_add_f32_e32 v126, v119, v125
	v_sub_f32_e32 v127, v112, v126
	v_sub_f32_e32 v112, v112, v127
	v_sub_f32_e32 v119, v126, v119
	v_sub_f32_e32 v112, v112, v126
	v_sub_f32_e32 v119, v119, v125
	v_add_f32_e32 v112, v113, v112
	v_add_f32_e32 v112, v119, v112
	v_add_f32_e32 v113, v127, v112
	v_mul_f32_e32 v119, v122, v113
	v_sub_f32_e32 v125, v127, v113
	v_mul_f32_e32 v126, v121, v119
	v_add_f32_e32 v112, v112, v125
	v_add_f32_e32 v125, v118, v119
	v_fma_f32 v121, v119, v121, -v126
	v_sub_f32_e32 v118, v125, v118
	v_fmac_f32_e32 v121, v119, v111
	v_sub_f32_e32 v111, v119, v118
	v_add_f32_e32 v118, v126, v121
	v_sub_f32_e32 v119, v118, v126
	v_sub_f32_e32 v126, v113, v118
	v_sub_f32_e32 v113, v113, v126
	v_sub_f32_e32 v113, v113, v118
	v_cvt_f32_i32_e32 v110, v110
	v_sub_f32_e32 v119, v119, v121
	v_add_f32_e32 v112, v112, v113
	v_add_f32_e32 v112, v119, v112
	v_add_f32_e32 v112, v126, v112
	v_mul_f32_e32 v112, v122, v112
	v_add_f32_e32 v111, v111, v112
	v_mul_f32_e32 v119, 0x3f317218, v110
	v_add_f32_e32 v112, v125, v111
	v_fma_f32 v121, v110, s71, -v119
; __device__ __forceinline__ unsigned cvt_pk_bf16(float lo, float hi) { unsigned r; asm volatile("v_cvt_pk_bf16_f32 %0, %1, %2" : "=v"(r) : "v"(lo), "v"(hi)); return r; }
; __device__ __forceinline__ float bflo(unsigned w) { return __uint_as_float(w << 16); }
; __device__ __forceinline__ float bfhi(unsigned w) { return __uint_as_float(w & 0xffff0000u); }
; __device__ __forceinline__ float sigm(float x) { return __builtin_amdgcn_rcpf(1.f + __expf(-x)); }
; template <bool PASS2> ...
;     ...
;                 const float ba = pba[cb], bx = pbx[cb], sp = log1pf(__expf(-plm[cb]));
; #pragma unroll
;                 for (int tb = 0; tb < 2; ++tb)
; #pragma unroll
;                     for (int q = 0; q < 4; ++q) { const float xv = xl[(tb * 16 + fq * 4 + q) * 68 + cb * 16 + fr];
;                         const float r = sigm(ga[tb][q] + ba), ig = sigm(gx[tb][q] + bx), la = -8.f * r * sp;
;                         const float aa = __expf(la), om = (1.f - aa) * (1.f + aa), bb = __builtin_amdgcn_sqrtf(om) * (ig * xv);
;                         const unsigned pk = cvt_pk_bf16(la, bb);
;                         labd[(size_t)(tb * 16 + q) * 256 + cb * 16] = pk;
;                         av[tb][q] = __expf(bflo(pk)); bv[tb][q] = bfhi(pk); }
	v_fmac_f32_e32 v121, 0xb102e308, v110
	v_sub_f32_e32 v110, v112, v125
	v_mul_f32_e32 v113, v112, v112
	v_sub_f32_e32 v110, v111, v110
	v_add_f32_e32 v111, v119, v121
	v_fmamk_f32 v118, v113, 0x3e9b6dac, v198
	v_sub_f32_e32 v119, v111, v119
	v_fmaak_f32 v118, v113, v118, 0x3f2aaada
	v_sub_f32_e32 v119, v121, v119
	v_ldexp_f32 v121, v112, 1
	v_mul_f32_e32 v112, v112, v113
	v_mul_f32_e32 v112, v112, v118
	v_add_f32_e32 v113, v121, v112
	v_sub_f32_e32 v118, v113, v121
	v_ldexp_f32 v110, v110, 1
	v_sub_f32_e32 v112, v112, v118
	v_add_f32_e32 v110, v110, v112
	v_add_f32_e32 v112, v113, v110
	v_sub_f32_e32 v113, v112, v113
	v_sub_f32_e32 v110, v110, v113
	v_add_f32_e32 v113, v111, v112
	v_sub_f32_e32 v118, v113, v111
	v_sub_f32_e32 v121, v113, v118
	v_sub_f32_e32 v111, v111, v121
	v_sub_f32_e32 v112, v112, v118
	v_add_f32_e32 v111, v112, v111
	v_add_f32_e32 v112, v119, v110
	v_sub_f32_e32 v118, v112, v119
	v_add_f32_e32 v111, v112, v111
	v_sub_f32_e32 v121, v112, v118
	v_add_f32_e32 v112, v113, v111
	v_sub_f32_e32 v119, v119, v121
	v_sub_f32_e32 v110, v110, v118
	v_sub_f32_e32 v113, v112, v113
	v_add_f32_e32 v110, v110, v119
	v_sub_f32_e32 v111, v111, v113
	v_add_f32_e32 v110, v110, v111
	v_add_f32_e32 v74, 1.0, v74
	v_add_f32_e32 v110, v112, v110
	v_cmp_neq_f32_e32 vcc, s12, v120
	v_rcp_f32_e32 v74, v74
	v_mul_f32_e32 v75, 0xbfb8aa3b, v75
	v_cndmask_b32_e32 v110, v203, v110, vcc
	v_cmp_ngt_f32_e32 vcc, -1.0, v120
	v_mul_f32_e32 v74, 0xc1000000, v74
	v_exp_f32_e32 v75, v75
	v_cndmask_b32_e32 v110, v204, v110, vcc
	v_cmp_neq_f32_e32 vcc, -1.0, v120
	v_add_f32_e32 v82, v124, v82
	v_add_f32_e32 v75, 1.0, v75
	v_cndmask_b32_e32 v110, v205, v110, vcc
	v_cmp_lt_f32_e64 vcc, |v120|, s13
	v_mul_f32_e32 v82, 0xbfb8aa3b, v82
	v_rcp_f32_e32 v75, v75
	v_cndmask_b32_e32 v118, v110, v120, vcc
	v_mul_f32_e32 v74, v74, v118
	v_mul_f32_e32 v110, 0x3fb8aa3b, v74
	v_exp_f32_e32 v110, v110
	v_exp_f32_e32 v82, v82
	v_mul_f32_e32 v75, 0xc1000000, v75
	ds_read_b32 v119, v93
	v_sub_f32_e32 v111, 1.0, v110
	v_add_f32_e32 v110, 1.0, v110
	v_mul_f32_e32 v110, v111, v110
	v_sqrt_f32_e32 v120, v110
	v_mfma_f32_16x16x32_bf16 v[110:113], v[18:21], v[78:81], v[114:117]
	v_add_f32_e32 v79, v124, v83
	v_add_f32_e32 v82, 1.0, v82
	v_mul_f32_e32 v79, 0xbfb8aa3b, v79
	v_mul_f32_e32 v75, v75, v118
	v_rcp_f32_e32 v82, v82
	v_exp_f32_e32 v79, v79
	v_mul_f32_e32 v80, 0x3fb8aa3b, v75
	v_exp_f32_e32 v80, v80
	s_waitcnt lgkmcnt(0)
	v_mul_f32_e32 v78, v119, v82
	v_add_f32_e32 v79, 1.0, v79
	v_mul_f32_e32 v78, v78, v120
	v_cvt_pk_bf16_f32 v74, v74, v78
	ds_read_b32 v81, v93 offset:272
	v_rcp_f32_e32 v82, v79
	v_sub_f32_e32 v79, 1.0, v80
	v_add_f32_e32 v80, 1.0, v80
	v_mul_f32_e32 v79, v79, v80
	v_sqrt_f32_e32 v80, v79
	global_store_dword v[100:101], v74, off
	v_lshlrev_b32_e32 v78, 16, v74
	v_and_b32_e32 v79, 0xffff0000, v74
	s_waitcnt lgkmcnt(0)
	v_mul_f32_e32 v74, v82, v81
	v_mul_f32_e32 v74, v74, v80
	v_cvt_pk_bf16_f32 v74, v75, v74
	v_add_f32_e32 v75, v123, v76
	v_mul_f32_e32 v75, 0xbfb8aa3b, v75
	v_exp_f32_e32 v75, v75
	v_add_f32_e32 v80, v124, v84
	v_mul_f32_e32 v80, 0xbfb8aa3b, v80
	v_exp_f32_e32 v80, v80
	v_add_f32_e32 v75, 1.0, v75
	v_rcp_f32_e32 v75, v75
	ds_read_b32 v82, v93 offset:544
	v_add_f32_e32 v80, 1.0, v80
	v_rcp_f32_e32 v83, v80
	v_mul_f32_e32 v75, 0xc1000000, v75
	v_mul_f32_e32 v75, v75, v118
	v_mul_f32_e32 v81, 0x3fb8aa3b, v75
	v_exp_f32_e32 v81, v81
	global_store_dword v[100:101], v74, off offset:1024
	v_lshlrev_b32_e32 v76, 16, v74
	v_add_f32_e32 v70, v123, v70
	v_sub_f32_e32 v80, 1.0, v81
	v_add_f32_e32 v81, 1.0, v81
	v_mul_f32_e32 v80, v80, v81
	v_sqrt_f32_e32 v81, v80
	v_and_b32_e32 v80, 0xffff0000, v74
	s_waitcnt lgkmcnt(0)
; __device__ __forceinline__ unsigned cvt_pk_bf16(float lo, float hi) { unsigned r; asm volatile("v_cvt_pk_bf16_f32 %0, %1, %2" : "=v"(r) : "v"(lo), "v"(hi)); return r; }
; __device__ __forceinline__ float bflo(unsigned w) { return __uint_as_float(w << 16); }
; __device__ __forceinline__ float bfhi(unsigned w) { return __uint_as_float(w & 0xffff0000u); }
; __device__ __forceinline__ float sigm(float x) { return __builtin_amdgcn_rcpf(1.f + __expf(-x)); }
; template <bool PASS2> ...
;     ...
;                 for (int tb = 0; tb < 2; ++tb)
; #pragma unroll
;                     for (int q = 0; q < 4; ++q) { const float xv = xl[(tb * 16 + fq * 4 + q) * 68 + cb * 16 + fr];
;                         const float r = sigm(ga[tb][q] + ba), ig = sigm(gx[tb][q] + bx), la = -8.f * r * sp;
;                         const float aa = __expf(la), om = (1.f - aa) * (1.f + aa), bb = __builtin_amdgcn_sqrtf(om) * (ig * xv);
;                         const unsigned pk = cvt_pk_bf16(la, bb);
;                         labd[(size_t)(tb * 16 + q) * 256 + cb * 16] = pk;
;                         av[tb][q] = __expf(bflo(pk)); bv[tb][q] = bfhi(pk); }
;             } else {
; #pragma unroll
;                 for (int tb = 0; tb < 2; ++tb)
; #pragma unroll
;                     for (int q = 0; q < 4; ++q) { const unsigned pk = pkv[cb][tb][q]; av[tb][q] = __expf(bflo(pk)); bv[tb][q] = bfhi(pk); }
;             }
; #pragma unroll
;             for (int tb = 0; tb < 2; ++tb) {
;                 Ap[tb] = (av[tb][0] * av[tb][1]) * (av[tb][2] * av[tb][3]);
;                 Bp[tb] = d == 0 ? ((bv[tb][0] * av[tb][1] + bv[tb][1]) * av[tb][2] + bv[tb][2]) * av[tb][3] + bv[tb][3]
;                                 : ((bv[tb][3] * av[tb][2] + bv[tb][2]) * av[tb][1] + bv[tb][1]) * av[tb][0] + bv[tb][0];
	v_mul_f32_e32 v74, v83, v82
	v_mul_f32_e32 v70, 0xbfb8aa3b, v70
	v_mul_f32_e32 v74, v74, v81
	v_cvt_pk_bf16_f32 v74, v75, v74
	v_add_f32_e32 v75, v123, v77
	v_mul_f32_e32 v75, 0xbfb8aa3b, v75
	v_exp_f32_e32 v75, v75
	v_add_f32_e32 v81, v124, v85
	v_mul_f32_e32 v81, 0xbfb8aa3b, v81
	v_exp_f32_e32 v81, v81
	v_add_f32_e32 v75, 1.0, v75
	v_rcp_f32_e32 v75, v75
	v_exp_f32_e32 v70, v70
	ds_read_b32 v83, v93 offset:816
	v_add_f32_e32 v81, 1.0, v81
	v_mul_f32_e32 v75, 0xc1000000, v75
	v_mul_f32_e32 v75, v75, v118
	v_mul_f32_e32 v82, 0x3fb8aa3b, v75
	v_exp_f32_e32 v82, v82
	v_rcp_f32_e32 v81, v81
	v_add_f32_e32 v70, 1.0, v70
	v_rcp_f32_e32 v70, v70
	v_sub_f32_e32 v84, 1.0, v82
	v_add_f32_e32 v82, 1.0, v82
	v_mul_f32_e32 v82, v84, v82
	v_sqrt_f32_e32 v82, v82
	s_waitcnt lgkmcnt(0)
	v_mul_f32_e32 v81, v81, v83
	global_store_dword v[100:101], v74, off offset:2048
	v_mul_f32_e32 v70, 0xc1000000, v70
	v_mul_f32_e32 v81, v81, v82
	v_cvt_pk_bf16_f32 v81, v75, v81
	v_add_f32_e32 v75, v124, v110
	v_mul_f32_e32 v75, 0xbfb8aa3b, v75
	v_add_f32_e32 v71, v123, v71
	v_exp_f32_e32 v75, v75
	v_mul_f32_e32 v70, v70, v118
	v_mul_f32_e32 v71, 0xbfb8aa3b, v71
	v_mul_f32_e32 v82, 0x3fb8aa3b, v70
	v_exp_f32_e32 v71, v71
	v_exp_f32_e32 v82, v82
	ds_read_b32 v83, v93 offset:4352
	v_add_f32_e32 v75, 1.0, v75
	v_rcp_f32_e32 v75, v75
	v_add_f32_e32 v71, 1.0, v71
	v_sub_f32_e32 v84, 1.0, v82
	v_add_f32_e32 v82, 1.0, v82
	v_rcp_f32_e32 v71, v71
	v_mul_f32_e32 v82, v84, v82
	v_sqrt_f32_e32 v84, v82
	v_lshlrev_b32_e32 v77, 16, v74
	v_and_b32_e32 v82, 0xffff0000, v74
	s_waitcnt lgkmcnt(0)
	v_mul_f32_e32 v74, v75, v83
	v_add_f32_e32 v83, v124, v111
	v_mul_f32_e32 v83, 0xbfb8aa3b, v83
	v_mul_f32_e32 v71, 0xc1000000, v71
	v_exp_f32_e32 v83, v83
	v_mul_f32_e32 v71, v71, v118
	v_mul_f32_e32 v74, v74, v84
	v_mul_f32_e32 v84, 0x3fb8aa3b, v71
	v_exp_f32_e32 v84, v84
	global_store_dword v[100:101], v81, off offset:3072
	v_cvt_pk_bf16_f32 v70, v70, v74
	ds_read_b32 v85, v93 offset:4624
	v_add_f32_e32 v83, 1.0, v83
	v_rcp_f32_e32 v83, v83
	v_sub_f32_e32 v110, 1.0, v84
	v_add_f32_e32 v84, 1.0, v84
	v_mul_f32_e32 v84, v110, v84
	v_add_f32_e32 v72, v123, v72
	v_sqrt_f32_e32 v84, v84
	v_mul_f32_e32 v72, 0xbfb8aa3b, v72
	s_waitcnt lgkmcnt(0)
	v_mul_f32_e32 v83, v83, v85
	v_exp_f32_e32 v85, v72
	v_add_co_u32_e32 v74, vcc, s0, v100
	v_mul_f32_e32 v72, v83, v84
	s_nop 0
	v_addc_co_u32_e32 v75, vcc, 0, v101, vcc
	global_store_dword v[74:75], v70, off
	v_cvt_pk_bf16_f32 v72, v71, v72
	v_add_f32_e32 v71, 1.0, v85
	v_rcp_f32_e32 v71, v71
	v_add_f32_e32 v83, v124, v112
	v_mul_f32_e32 v83, 0xbfb8aa3b, v83
	v_exp_f32_e32 v83, v83
	v_mul_f32_e32 v71, 0xc1000000, v71
	v_mul_f32_e32 v71, v71, v118
	v_mul_f32_e32 v84, 0x3fb8aa3b, v71
	v_exp_f32_e32 v84, v84
	ds_read_b32 v85, v93 offset:4896
	v_add_f32_e32 v83, 1.0, v83
	v_rcp_f32_e32 v83, v83
	v_sub_f32_e32 v110, 1.0, v84
	v_add_f32_e32 v84, 1.0, v84
	v_mul_f32_e32 v84, v110, v84
	v_add_f32_e32 v73, v123, v73
	v_sqrt_f32_e32 v84, v84
	v_mul_f32_e32 v73, 0xbfb8aa3b, v73
	v_exp_f32_e32 v73, v73
	s_waitcnt lgkmcnt(0)
	v_mul_f32_e32 v83, v83, v85
	v_mul_f32_e32 v83, v83, v84
	global_store_dword v[74:75], v72, off offset:1024
	v_cvt_pk_bf16_f32 v83, v71, v83
	v_add_f32_e32 v71, 1.0, v73
	v_rcp_f32_e32 v71, v71
	v_add_f32_e32 v73, v124, v113
	v_mul_f32_e32 v73, 0xbfb8aa3b, v73
	v_exp_f32_e32 v73, v73
	v_mul_f32_e32 v71, 0xc1000000, v71
	v_mul_f32_e32 v71, v71, v118
	v_mul_f32_e32 v84, 0x3fb8aa3b, v71
	v_exp_f32_e32 v84, v84
	ds_read_b32 v110, v93 offset:5168
	v_add_f32_e32 v73, 1.0, v73
	v_rcp_f32_e32 v73, v73
	v_sub_f32_e32 v85, 1.0, v84
	v_add_f32_e32 v84, 1.0, v84
	v_mul_f32_e32 v84, v85, v84
	v_mul_f32_e32 v78, 0x3fb8aa3b, v78
	v_mul_f32_e32 v76, 0x3fb8aa3b, v76
	v_mul_f32_e32 v77, 0x3fb8aa3b, v77
	v_sqrt_f32_e32 v84, v84
	v_exp_f32_e32 v78, v78
	v_exp_f32_e32 v76, v76
	v_exp_f32_e32 v77, v77
	s_waitcnt lgkmcnt(0)
	v_mul_f32_e32 v73, v73, v110
	v_and_b32_e32 v85, 0xffff0000, v81
	v_mul_f32_e32 v73, v73, v84
	s_and_b64 vcc, exec, s[50:51]
	global_store_dword v[74:75], v83, off offset:2048
	v_cvt_pk_bf16_f32 v84, v71, v73
	global_store_dword v[74:75], v84, off offset:3072
	s_cbranch_vccz .LBB0_504
	v_fma_f32 v71, v77, v85, v82
	v_fma_f32 v71, v76, v71, v80
	v_fma_f32 v73, v78, v71, v79
	s_mov_b64 s[20:21], 0

; template <bool PASS2> ...
;     ...
;             float PA[8], PB[8];
; #pragma unroll
;             for (int e = 0; e < 8; ++e) { PA[e] = __shfl(Ap[e >> 2], (e & 3) * 16 + fr); PB[e] = __shfl(Bp[e >> 2], (e & 3) * 16 + fr); }
;             const size_t si = ((size_t)(b * NCH + c) * 2 + d) * 256 + chn;
;             if (!PASS2) {
;                 float At = 1.f, Bt = 0.f;
; #pragma unroll
;                 for (int e2 = 0; e2 < 8; ++e2) { const int e = d == 0 ? e2 : 7 - e2; Bt = PA[e] * Bt + PB[e]; At *= PA[e]; }
;                 if (fq == 0) { LRA[si] = At; LRB[si] = Bt; }
.LBB0_511:
	v_mul_f32_e32 v70, v79, v70
	v_mul_f32_e32 v72, v72, v80
	v_mul_f32_e32 v82, v70, v72
	v_mul_f32_e32 v70, v78, v76
	v_mul_f32_e32 v71, v77, v71
	v_and_b32_e32 v77, 64, v199
	v_mul_f32_e32 v78, v70, v71
	v_or_b32_e32 v70, v77, v91
	v_or_b32_e32 v77, v77, v95
	v_lshlrev_b32_e32 v76, 2, v70
	v_lshl_or_b32 v77, v77, 2, v206
	ds_bpermute_b32 v83, v76, v78
	ds_bpermute_b32 v70, v76, v73
	ds_bpermute_b32 v112, v76, v78 offset:64
	ds_bpermute_b32 v71, v76, v73 offset:64
	ds_bpermute_b32 v85, v76, v78 offset:128
	ds_bpermute_b32 v72, v76, v73 offset:128
	ds_bpermute_b32 v113, v77, v78
	ds_bpermute_b32 v73, v77, v73
	ds_bpermute_b32 v110, v76, v82
	ds_bpermute_b32 v81, v76, v114
	ds_bpermute_b32 v111, v76, v82 offset:64
	ds_bpermute_b32 v80, v76, v114 offset:64
	ds_bpermute_b32 v84, v76, v82 offset:128
	ds_bpermute_b32 v79, v76, v114 offset:128
	ds_bpermute_b32 v82, v77, v82
	ds_bpermute_b32 v78, v77, v114
	s_mov_b32 s5, s89
	s_lshl_b64 s[4:5], s[4:5], 8
	s_or_b64 s[66:67], s[4:5], s[46:47]
	s_and_saveexec_b64 s[4:5], s[36:37]
	s_cbranch_execz .LBB0_513
	s_cmp_eq_u32 s64, 1
	s_cselect_b64 vcc, -1, 0
	s_cmp_eq_u32 s64, 2
	s_waitcnt lgkmcnt(0)
	v_cndmask_b32_e32 v116, v83, v112, vcc
	s_cselect_b64 vcc, -1, 0
	s_cmp_eq_u32 s64, 3
	v_cndmask_b32_e32 v116, v116, v85, vcc
	s_cselect_b64 vcc, -1, 0
	s_cmp_eq_u32 s64, 4
	v_cndmask_b32_e32 v116, v116, v113, vcc
	s_cselect_b64 vcc, -1, 0
	s_cmp_eq_u32 s64, 5
	v_cndmask_b32_e32 v116, v116, v110, vcc
	s_cselect_b64 vcc, -1, 0
	s_cmp_eq_u32 s64, 6
	v_cndmask_b32_e32 v116, v116, v111, vcc
	s_cselect_b64 vcc, -1, 0
	s_cmp_eq_u32 s64, 7
	v_cndmask_b32_e32 v116, v116, v84, vcc
	s_cselect_b64 vcc, -1, 0
	s_cmp_eq_u32 s62, 1
	v_cndmask_b32_e32 v116, v116, v82, vcc
	s_cselect_b64 vcc, -1, 0
	s_cmp_eq_u32 s62, 2
	v_cndmask_b32_e32 v117, v83, v112, vcc
	s_cselect_b64 vcc, -1, 0
	s_cmp_eq_u32 s62, 3
	v_cndmask_b32_e32 v117, v117, v85, vcc
	s_cselect_b64 vcc, -1, 0
	s_cmp_eq_u32 s62, 4
	v_cndmask_b32_e32 v117, v117, v113, vcc
	s_cselect_b64 vcc, -1, 0
	s_cmp_eq_u32 s62, 5
	v_cndmask_b32_e32 v117, v117, v110, vcc
	s_cselect_b64 vcc, -1, 0
	s_cmp_eq_u32 s62, 6
	v_cndmask_b32_e32 v117, v117, v111, vcc
	s_cselect_b64 vcc, -1, 0
	s_cmp_eq_u32 s62, 7
	v_cndmask_b32_e32 v117, v117, v84, vcc
	s_cselect_b64 vcc, -1, 0
	s_cmp_eq_u32 s60, 1
	v_cndmask_b32_e32 v117, v117, v82, vcc
	s_cselect_b64 vcc, -1, 0
	s_cmp_eq_u32 s60, 2
	v_cndmask_b32_e32 v119, v83, v112, vcc
	s_cselect_b64 vcc, -1, 0
	s_cmp_eq_u32 s60, 3
	v_cndmask_b32_e32 v119, v119, v85, vcc
	s_cselect_b64 vcc, -1, 0
	s_cmp_eq_u32 s60, 4
	v_cndmask_b32_e32 v119, v119, v113, vcc
	s_cselect_b64 vcc, -1, 0
	s_cmp_eq_u32 s60, 5
	v_cndmask_b32_e32 v119, v119, v110, vcc
	s_cselect_b64 vcc, -1, 0
	s_cmp_eq_u32 s60, 6
	v_cndmask_b32_e32 v119, v119, v111, vcc
	s_cselect_b64 vcc, -1, 0
	s_cmp_eq_u32 s60, 7
	v_cndmask_b32_e32 v119, v119, v84, vcc
	s_cselect_b64 vcc, -1, 0
	s_cmp_eq_u32 s58, 1
	v_cndmask_b32_e32 v119, v119, v82, vcc
	s_cselect_b64 vcc, -1, 0
	s_cmp_eq_u32 s58, 2
	v_cndmask_b32_e32 v120, v83, v112, vcc
	s_cselect_b64 vcc, -1, 0
	s_cmp_eq_u32 s58, 3
	v_cndmask_b32_e32 v120, v120, v85, vcc
	s_cselect_b64 vcc, -1, 0
	s_cmp_eq_u32 s58, 4
	v_cndmask_b32_e32 v120, v120, v113, vcc
	s_cselect_b64 vcc, -1, 0
	s_cmp_eq_u32 s58, 5
	v_cndmask_b32_e32 v120, v120, v110, vcc
	s_cselect_b64 vcc, -1, 0
	s_cmp_eq_u32 s58, 6
	v_cndmask_b32_e32 v120, v120, v111, vcc
	s_cselect_b64 vcc, -1, 0
	s_cmp_eq_u32 s58, 7
	v_cndmask_b32_e32 v120, v120, v84, vcc
	s_cselect_b64 vcc, -1, 0
	s_cmp_eq_u32 s56, 1
	v_cndmask_b32_e32 v120, v120, v82, vcc
	s_cselect_b64 vcc, -1, 0
	s_cmp_eq_u32 s56, 2
	v_cndmask_b32_e32 v121, v83, v112, vcc
	s_cselect_b64 vcc, -1, 0
	s_cmp_eq_u32 s56, 3
	v_cndmask_b32_e32 v121, v121, v85, vcc
	s_cselect_b64 vcc, -1, 0
	s_cmp_eq_u32 s56, 4
	v_cndmask_b32_e32 v121, v121, v113, vcc
	s_cselect_b64 vcc, -1, 0
	s_cmp_eq_u32 s56, 5
	v_cndmask_b32_e32 v121, v121, v110, vcc
	s_cselect_b64 vcc, -1, 0
	s_cmp_eq_u32 s56, 6
	v_cndmask_b32_e32 v121, v121, v111, vcc
	s_cselect_b64 vcc, -1, 0
	s_cmp_eq_u32 s56, 7
	v_cndmask_b32_e32 v121, v121, v84, vcc
	s_cselect_b64 vcc, -1, 0
	s_cmp_eq_u32 s54, 1
	v_cndmask_b32_e32 v121, v121, v82, vcc
	s_cselect_b64 vcc, -1, 0
	s_cmp_eq_u32 s54, 2
	v_cndmask_b32_e32 v122, v83, v112, vcc
	s_cselect_b64 vcc, -1, 0
	s_cmp_eq_u32 s54, 3
	v_cndmask_b32_e32 v122, v122, v85, vcc
	s_cselect_b64 vcc, -1, 0
	s_cmp_eq_u32 s54, 4
	v_cndmask_b32_e32 v122, v122, v113, vcc
	s_cselect_b64 vcc, -1, 0
	s_cmp_eq_u32 s54, 5
	v_cndmask_b32_e32 v122, v122, v110, vcc
	s_cselect_b64 vcc, -1, 0
	s_cmp_eq_u32 s54, 6
	v_cndmask_b32_e32 v122, v122, v111, vcc
	s_cselect_b64 vcc, -1, 0
	s_cmp_eq_u32 s54, 7
	v_cndmask_b32_e32 v122, v122, v84, vcc
	s_cselect_b64 vcc, -1, 0
	s_cmp_eq_u32 s52, 1
	v_cndmask_b32_e32 v122, v122, v82, vcc
	s_cselect_b64 vcc, -1, 0
	s_cmp_eq_u32 s52, 2
	v_cndmask_b32_e32 v123, v83, v112, vcc
	s_cselect_b64 vcc, -1, 0
	s_cmp_eq_u32 s52, 3
	v_cndmask_b32_e32 v123, v123, v85, vcc
	s_cselect_b64 vcc, -1, 0
	s_cmp_eq_u32 s52, 4
	v_cndmask_b32_e32 v123, v123, v113, vcc
	s_cselect_b64 vcc, -1, 0
	s_cmp_eq_u32 s52, 5
	v_cndmask_b32_e32 v123, v123, v110, vcc
	s_cselect_b64 vcc, -1, 0
	s_cmp_eq_u32 s52, 6
	v_cndmask_b32_e32 v123, v123, v111, vcc
	s_cselect_b64 vcc, -1, 0
	s_cmp_eq_u32 s52, 7
	v_cndmask_b32_e32 v123, v123, v84, vcc
	s_cselect_b64 vcc, -1, 0
	s_cmp_eq_u32 s50, 1
	v_cndmask_b32_e32 v123, v123, v82, vcc
	s_cselect_b64 vcc, -1, 0
	s_cmp_eq_u32 s50, 2
	v_cndmask_b32_e32 v83, v83, v112, vcc
	s_cselect_b64 vcc, -1, 0
	s_cmp_eq_u32 s50, 3
	v_cndmask_b32_e32 v83, v83, v85, vcc
	s_cselect_b64 vcc, -1, 0
	s_cmp_eq_u32 s50, 4
	v_cndmask_b32_e32 v83, v83, v113, vcc
; #define MFMA16(a, b, c) __builtin_amdgcn_mfma_f32_16x16x32_bf16((a), (b), (c), 0, 0, 0)
; template <bool PASS2> ...
;     ...
;                 f32x4 ga[2], gx[2];
;                 ga[0] = ga[1] = gx[0] = gx[1] = (f32x4){0.f, 0.f, 0.f, 0.f};
; #pragma unroll
;                 for (int ks = 0; ks < 2; ++ks) {
; #pragma unroll
;                     for (int tb = 0; tb < 2; ++tb) { ga[tb] = MFMA16(af[tb][ks], wfa[cb][ks], ga[tb]); gx[tb] = MFMA16(af[tb][ks], wfx[cb][ks], gx[tb]); } }
;                 const float ba = pba[cb], bx = pbx[cb], sp = log1pf(__expf(-plm[cb]));
;     ...
;                 float At = 1.f, Bt = 0.f;
; #pragma unroll
;                 for (int e2 = 0; e2 < 8; ++e2) { const int e = d == 0 ? e2 : 7 - e2; Bt = PA[e] * Bt + PB[e]; At *= PA[e]; }
;                 if (fq == 0) { LRA[si] = At; LRB[si] = Bt; }
	s_cselect_b64 vcc, -1, 0
	s_cmp_eq_u32 s50, 5
	v_cndmask_b32_e32 v83, v83, v110, vcc
	s_cselect_b64 vcc, -1, 0
	s_cmp_eq_u32 s50, 6
	v_cndmask_b32_e32 v83, v83, v111, vcc
	s_cselect_b64 vcc, -1, 0
	v_cndmask_b32_e32 v83, v83, v84, vcc
	v_cndmask_b32_e64 v84, v78, v70, s[48:49]
	v_fmac_f32_e32 v84, 0, v116
	v_cndmask_b32_e64 v85, v79, v71, s[48:49]
	v_fmac_f32_e32 v85, v117, v84
	v_cndmask_b32_e64 v84, v80, v72, s[48:49]
	v_mul_f32_e32 v118, v116, v117
	v_fmac_f32_e32 v84, v119, v85
	v_cndmask_b32_e64 v85, v81, v73, s[48:49]
	v_mul_f32_e32 v118, v119, v118
	v_fmac_f32_e32 v85, v120, v84
	v_cndmask_b32_e64 v73, v73, v81, s[48:49]
	v_mul_f32_e32 v118, v120, v118
	s_cmp_eq_u32 s50, 7
	v_fmac_f32_e32 v73, v121, v85
	v_cndmask_b32_e64 v72, v72, v80, s[48:49]
	v_mul_f32_e32 v118, v121, v118
	s_cselect_b64 vcc, -1, 0
	v_fmac_f32_e32 v72, v122, v73
	v_cndmask_b32_e64 v71, v71, v79, s[48:49]
	v_mov_b32_e32 v115, s67
	v_or_b32_e32 v114, s66, v90
	v_mul_f32_e32 v118, v122, v118
	v_cndmask_b32_e32 v82, v83, v82, vcc
	v_fmac_f32_e32 v71, v123, v72
	v_cndmask_b32_e64 v78, v70, v78, s[48:49]
	v_mul_f32_e32 v118, v123, v118
	v_fmac_f32_e32 v78, v82, v71
	v_lshlrev_b64 v[70:71], 2, v[114:115]
	v_mul_f32_e32 v83, v82, v118
	v_lshl_add_u64 v[72:73], s[44:45], 0, v[70:71]
	v_lshl_add_u64 v[70:71], s[42:43], 0, v[70:71]
	global_store_dword v[70:71], v83, off
	global_store_dword v[72:73], v78, off
.LBB0_513:
	s_or_b64 exec, exec, s[4:5]
	s_waitcnt lgkmcnt(0)
	v_mfma_f32_16x16x32_bf16 v[70:73], v[2:5], v[58:61], 0
	s_mov_b64 s[4:5], -1
	v_mfma_f32_16x16x32_bf16 v[78:81], v[2:5], v[66:69], 0
	v_mfma_f32_16x16x32_bf16 v[58:61], v[14:17], v[58:61], 0
	v_mfma_f32_16x16x32_bf16 v[82:85], v[14:17], v[66:69], 0
	v_mfma_f32_16x16x32_bf16 v[70:73], v[6:9], v[54:57], v[70:73]
	v_mfma_f32_16x16x32_bf16 v[66:69], v[6:9], v[62:65], v[78:81]
	v_mfma_f32_16x16x32_bf16 v[58:61], v[18:21], v[54:57], v[58:61]
	v_mfma_f32_16x16x32_bf16 v[54:57], v[18:21], v[62:65], v[82:85]
	v_mul_f32_e32 v62, 0xbfb8aa3b, v109
	v_exp_f32_e32 v64, v62
	s_nop 3
	v_add_f32_e32 v67, v107, v67
	v_mul_f32_e32 v67, 0xbfb8aa3b, v67
	v_exp_f32_e32 v67, v67
	v_add_f32_e32 v65, 1.0, v64
	v_add_f32_e32 v62, -1.0, v65
	v_sub_f32_e32 v63, v62, v65
	v_add_f32_e32 v63, 1.0, v63
	v_sub_f32_e32 v62, v64, v62
	v_add_f32_e32 v78, v62, v63
	v_frexp_mant_f32_e32 v62, v65
	v_cmp_gt_f32_e32 vcc, s70, v62
	v_cvt_f64_f32_e32 v[62:63], v65
	v_frexp_exp_i32_f64_e32 v62, v[62:63]
	v_subbrev_co_u32_e32 v62, vcc, 0, v62, vcc
	v_sub_u32_e32 v63, 0, v62
	v_ldexp_f32 v65, v65, v63
	v_ldexp_f32 v63, v78, v63
	v_add_f32_e32 v78, -1.0, v65
	v_add_f32_e32 v79, 1.0, v78
	v_sub_f32_e32 v79, v65, v79
	v_add_f32_e32 v79, v63, v79
	v_add_f32_e32 v80, v78, v79
	v_sub_f32_e32 v78, v80, v78
	v_sub_f32_e32 v78, v79, v78
	v_add_f32_e32 v79, 1.0, v65
	v_add_f32_e32 v81, -1.0, v79
	v_sub_f32_e32 v65, v65, v81
	v_add_f32_e32 v63, v63, v65
	v_add_f32_e32 v65, v79, v63
	v_sub_f32_e32 v79, v65, v79
	v_sub_f32_e32 v63, v63, v79
	v_rcp_f32_e32 v79, v65
	v_cvt_f32_i32_e32 v62, v62
	v_cmp_neq_f32_e32 vcc, s12, v64
	v_add_f32_e32 v67, 1.0, v67
	v_mul_f32_e32 v81, v80, v79
	v_mul_f32_e32 v82, v65, v81
	v_fma_f32 v83, v81, v65, -v82
	v_fmac_f32_e32 v83, v81, v63
	v_add_f32_e32 v84, v82, v83
	v_sub_f32_e32 v85, v80, v84
	v_sub_f32_e32 v80, v80, v85
	v_sub_f32_e32 v82, v84, v82
	v_sub_f32_e32 v80, v80, v84
	v_add_f32_e32 v78, v78, v80
	v_sub_f32_e32 v80, v82, v83
	v_add_f32_e32 v78, v80, v78
	v_add_f32_e32 v80, v85, v78
	v_mul_f32_e32 v82, v79, v80
	v_mul_f32_e32 v83, v65, v82
	v_fma_f32 v65, v82, v65, -v83
	v_fmac_f32_e32 v65, v82, v63
	v_sub_f32_e32 v63, v85, v80
	v_add_f32_e32 v63, v78, v63
	v_add_f32_e32 v78, v83, v65
	v_sub_f32_e32 v84, v80, v78
	v_sub_f32_e32 v80, v80, v84
	v_sub_f32_e32 v83, v78, v83
	v_sub_f32_e32 v78, v80, v78
	v_add_f32_e32 v63, v63, v78
	v_sub_f32_e32 v65, v83, v65
	v_add_f32_e32 v63, v65, v63
	v_add_f32_e32 v65, v81, v82
	v_add_f32_e32 v63, v84, v63
	v_sub_f32_e32 v78, v65, v81
	v_mul_f32_e32 v63, v79, v63
	v_sub_f32_e32 v78, v82, v78
	v_add_f32_e32 v63, v78, v63
	v_mul_f32_e32 v81, 0x3f317218, v62
	v_add_f32_e32 v78, v65, v63
	v_fma_f32 v82, v62, s71, -v81
	v_mul_f32_e32 v79, v78, v78
	v_fmac_f32_e32 v82, 0xb102e308, v62
	v_sub_f32_e32 v62, v78, v65
	v_fmamk_f32 v80, v79, 0x3e9b6dac, v198
	v_sub_f32_e32 v62, v63, v62
	v_add_f32_e32 v63, v81, v82
	v_fmaak_f32 v80, v79, v80, 0x3f2aaada
	v_sub_f32_e32 v65, v63, v81
	v_ldexp_f32 v81, v78, 1
	v_mul_f32_e32 v78, v78, v79
	v_mul_f32_e32 v78, v78, v80
	v_add_f32_e32 v79, v81, v78
	v_sub_f32_e32 v80, v79, v81
	v_ldexp_f32 v62, v62, 1
	v_sub_f32_e32 v78, v78, v80
	v_add_f32_e32 v62, v62, v78
	v_add_f32_e32 v78, v79, v62
	v_sub_f32_e32 v79, v78, v79
	v_sub_f32_e32 v62, v62, v79
	v_add_f32_e32 v79, v63, v78
	v_sub_f32_e32 v80, v79, v63
	v_sub_f32_e32 v81, v79, v80
	v_sub_f32_e32 v65, v82, v65
	v_sub_f32_e32 v63, v63, v81
	v_sub_f32_e32 v78, v78, v80
	v_add_f32_e32 v63, v78, v63
	v_add_f32_e32 v78, v65, v62
	v_sub_f32_e32 v80, v78, v65
	v_sub_f32_e32 v81, v78, v80
	v_sub_f32_e32 v65, v65, v81
	v_sub_f32_e32 v62, v62, v80
	v_add_f32_e32 v63, v78, v63
	v_add_f32_e32 v62, v62, v65
	v_add_f32_e32 v65, v79, v63
	v_sub_f32_e32 v78, v65, v79
	v_sub_f32_e32 v63, v63, v78
	v_add_f32_e32 v62, v62, v63
	v_add_f32_e32 v62, v65, v62
	v_cndmask_b32_e32 v62, v203, v62, vcc
	v_cmp_ngt_f32_e32 vcc, -1.0, v64
	v_add_f32_e32 v65, v107, v66
	v_mul_f32_e32 v65, 0xbfb8aa3b, v65
	v_cndmask_b32_e32 v62, v204, v62, vcc
	v_cmp_neq_f32_e32 vcc, -1.0, v64
	v_exp_f32_e32 v65, v65
	v_rcp_f32_e32 v67, v67
	v_cndmask_b32_e32 v62, v205, v62, vcc
	v_cmp_lt_f32_e64 vcc, |v64|, s13
	v_add_f32_e32 v65, 1.0, v65
	v_rcp_f32_e32 v65, v65
	v_cndmask_b32_e32 v63, v62, v64, vcc
	v_add_f32_e32 v64, v108, v70
	v_mul_f32_e32 v64, 0xbfb8aa3b, v64
	v_exp_f32_e32 v64, v64
	ds_read_b32 v62, v93 offset:64
	v_add_f32_e32 v68, v107, v68
	v_mul_f32_e32 v68, 0xbfb8aa3b, v68
	v_add_f32_e32 v64, 1.0, v64
	v_rcp_f32_e32 v64, v64
	s_waitcnt lgkmcnt(0)
; __device__ __forceinline__ unsigned cvt_pk_bf16(float lo, float hi) { unsigned r; asm volatile("v_cvt_pk_bf16_f32 %0, %1, %2" : "=v"(r) : "v"(lo), "v"(hi)); return r; }
; __device__ __forceinline__ float bflo(unsigned w) { return __uint_as_float(w << 16); }
; __device__ __forceinline__ float bfhi(unsigned w) { return __uint_as_float(w & 0xffff0000u); }
; __device__ __forceinline__ float sigm(float x) { return __builtin_amdgcn_rcpf(1.f + __expf(-x)); }
; template <bool PASS2> ...
;     ...
; #pragma unroll
;                 for (int tb = 0; tb < 2; ++tb)
; #pragma unroll
;                     for (int q = 0; q < 4; ++q) { const float xv = xl[(tb * 16 + fq * 4 + q) * 68 + cb * 16 + fr];
;                         const float r = sigm(ga[tb][q] + ba), ig = sigm(gx[tb][q] + bx), la = -8.f * r * sp;
;                         const float aa = __expf(la), om = (1.f - aa) * (1.f + aa), bb = __builtin_amdgcn_sqrtf(om) * (ig * xv);
;                         const unsigned pk = cvt_pk_bf16(la, bb);
;                         labd[(size_t)(tb * 16 + q) * 256 + cb * 16] = pk;
;                         av[tb][q] = __expf(bflo(pk)); bv[tb][q] = bfhi(pk); }
;             } else {
; #pragma unroll
;                 for (int tb = 0; tb < 2; ++tb)
; #pragma unroll
;                     for (int q = 0; q < 4; ++q) { const unsigned pk = pkv[cb][tb][q]; av[tb][q] = __expf(bflo(pk)); bv[tb][q] = bfhi(pk); }
;             }
; #pragma unroll
;             for (int tb = 0; tb < 2; ++tb) {
;                 Ap[tb] = (av[tb][0] * av[tb][1]) * (av[tb][2] * av[tb][3]);
;                 Bp[tb] = d == 0 ? ((bv[tb][0] * av[tb][1] + bv[tb][1]) * av[tb][2] + bv[tb][2]) * av[tb][3] + bv[tb][3]
;                                 : ((bv[tb][3] * av[tb][2] + bv[tb][2]) * av[tb][1] + bv[tb][1]) * av[tb][0] + bv[tb][0];
	v_mul_f32_e32 v62, v62, v65
	v_exp_f32_e32 v68, v68
	v_add_f32_e32 v58, v108, v58
	v_mul_f32_e32 v64, 0xc1000000, v64
	v_mul_f32_e32 v64, v63, v64
	v_mul_f32_e32 v66, 0x3fb8aa3b, v64
	v_exp_f32_e32 v66, v66
	v_add_f32_e32 v68, 1.0, v68
	v_rcp_f32_e32 v68, v68
	v_add_f32_e32 v69, v107, v69
	v_sub_f32_e32 v70, 1.0, v66
	v_add_f32_e32 v66, 1.0, v66
	v_mul_f32_e32 v66, v70, v66
	v_sqrt_f32_e32 v66, v66
	v_mul_f32_e32 v58, 0xbfb8aa3b, v58
	v_mul_f32_e32 v69, 0xbfb8aa3b, v69
	v_exp_f32_e32 v58, v58
	v_mul_f32_e32 v62, v62, v66
	v_add_f32_e32 v66, v108, v71
	v_mul_f32_e32 v66, 0xbfb8aa3b, v66
	v_exp_f32_e32 v66, v66
	v_cvt_pk_bf16_f32 v64, v64, v62
	ds_read_b32 v65, v93 offset:336
	global_store_dword v[100:101], v64, off offset:64
	v_add_f32_e32 v66, 1.0, v66
	v_rcp_f32_e32 v66, v66
	v_exp_f32_e32 v69, v69
	s_waitcnt lgkmcnt(0)
	v_mul_f32_e32 v65, v67, v65
	v_add_f32_e32 v58, 1.0, v58
	v_mul_f32_e32 v66, 0xc1000000, v66
	v_mul_f32_e32 v66, v63, v66
	v_mul_f32_e32 v70, 0x3fb8aa3b, v66
	v_exp_f32_e32 v70, v70
	v_add_f32_e32 v69, 1.0, v69
	v_rcp_f32_e32 v58, v58
	v_add_f32_e32 v59, v108, v59
	v_sub_f32_e32 v71, 1.0, v70
	v_add_f32_e32 v70, 1.0, v70
	v_mul_f32_e32 v70, v71, v70
	v_sqrt_f32_e32 v70, v70
	v_rcp_f32_e32 v69, v69
	v_mul_f32_e32 v59, 0xbfb8aa3b, v59
	v_add_f32_e32 v54, v107, v54
	v_mul_f32_e32 v65, v65, v70
	v_add_f32_e32 v70, v108, v72
	v_mul_f32_e32 v70, 0xbfb8aa3b, v70
	v_exp_f32_e32 v70, v70
	v_cvt_pk_bf16_f32 v66, v66, v65
	ds_read_b32 v67, v93 offset:608
	global_store_dword v[100:101], v66, off offset:1088
	v_add_f32_e32 v70, 1.0, v70
	v_rcp_f32_e32 v70, v70
	v_exp_f32_e32 v59, v59
	s_waitcnt lgkmcnt(0)
	v_mul_f32_e32 v67, v68, v67
	v_mul_f32_e32 v54, 0xbfb8aa3b, v54
	v_mul_f32_e32 v70, 0xc1000000, v70
	v_mul_f32_e32 v70, v63, v70
	v_mul_f32_e32 v71, 0x3fb8aa3b, v70
	v_exp_f32_e32 v71, v71
	v_exp_f32_e32 v54, v54
	v_mul_f32_e32 v58, 0xc1000000, v58
	v_mul_f32_e32 v58, v63, v58
	v_sub_f32_e32 v72, 1.0, v71
	v_add_f32_e32 v71, 1.0, v71
	v_mul_f32_e32 v71, v72, v71
	v_sqrt_f32_e32 v71, v71
	v_add_f32_e32 v59, 1.0, v59
	v_rcp_f32_e32 v59, v59
	v_add_f32_e32 v54, 1.0, v54
	v_mul_f32_e32 v67, v67, v71
	v_add_f32_e32 v71, v108, v73
	v_mul_f32_e32 v71, 0xbfb8aa3b, v71
	v_exp_f32_e32 v71, v71
	v_cvt_pk_bf16_f32 v68, v70, v67
	ds_read_b32 v70, v93 offset:880
	global_store_dword v[100:101], v68, off offset:2112
	v_add_f32_e32 v71, 1.0, v71
	v_rcp_f32_e32 v71, v71
	v_rcp_f32_e32 v54, v54
	s_waitcnt lgkmcnt(0)
	v_mul_f32_e32 v69, v69, v70
	v_mul_f32_e32 v59, 0xc1000000, v59
	v_mul_f32_e32 v71, 0xc1000000, v71
	v_mul_f32_e32 v71, v63, v71
	v_mul_f32_e32 v72, 0x3fb8aa3b, v71
	v_exp_f32_e32 v72, v72
	v_add_f32_e32 v55, v107, v55
	v_mul_f32_e32 v59, v63, v59
	v_mul_f32_e32 v55, 0xbfb8aa3b, v55
	v_sub_f32_e32 v73, 1.0, v72
	v_add_f32_e32 v72, 1.0, v72
	v_mul_f32_e32 v72, v73, v72
	v_sqrt_f32_e32 v72, v72
	v_exp_f32_e32 v55, v55
	v_add_f32_e32 v56, v107, v56
	v_mul_f32_e32 v56, 0xbfb8aa3b, v56
	v_mul_f32_e32 v69, v72, v69
	v_mul_f32_e32 v72, 0x3fb8aa3b, v58
	v_exp_f32_e32 v72, v72
	v_cvt_pk_bf16_f32 v70, v71, v69
	ds_read_b32 v71, v93 offset:4416
	global_store_dword v[100:101], v70, off offset:3136
	v_sub_f32_e32 v73, 1.0, v72
	v_add_f32_e32 v72, 1.0, v72
	v_mul_f32_e32 v72, v73, v72
	v_sqrt_f32_e32 v72, v72
	s_waitcnt lgkmcnt(0)
	v_mul_f32_e32 v54, v54, v71
	v_mul_f32_e32 v71, 0x3fb8aa3b, v59
	v_exp_f32_e32 v71, v71
	v_mul_f32_e32 v54, v72, v54
	v_cvt_pk_bf16_f32 v54, v58, v54
	ds_read_b32 v58, v93 offset:4688
	v_add_f32_e32 v55, 1.0, v55
	v_sub_f32_e32 v72, 1.0, v71
	v_add_f32_e32 v71, 1.0, v71
	v_rcp_f32_e32 v55, v55
	v_mul_f32_e32 v71, v72, v71
	v_sqrt_f32_e32 v71, v71
	global_store_dword v[74:75], v54, off offset:64
	s_waitcnt lgkmcnt(0)
	v_mul_f32_e32 v55, v55, v58
	v_exp_f32_e32 v56, v56
	v_mul_f32_e32 v55, v71, v55
	v_cvt_pk_bf16_f32 v55, v59, v55
	v_add_f32_e32 v59, v108, v60
	v_mul_f32_e32 v59, 0xbfb8aa3b, v59
	v_exp_f32_e32 v59, v59
	ds_read_b32 v58, v93 offset:4960
	v_add_f32_e32 v56, 1.0, v56
	v_rcp_f32_e32 v56, v56
	v_add_f32_e32 v59, 1.0, v59
	v_rcp_f32_e32 v59, v59
	global_store_dword v[74:75], v55, off offset:1088
	s_waitcnt lgkmcnt(0)
	v_mul_f32_e32 v56, v56, v58
	v_add_f32_e32 v57, v107, v57
	v_mul_f32_e32 v59, 0xc1000000, v59
	v_mul_f32_e32 v59, v63, v59
	v_mul_f32_e32 v60, 0x3fb8aa3b, v59
	v_exp_f32_e32 v60, v60
	v_mul_f32_e32 v57, 0xbfb8aa3b, v57
	v_exp_f32_e32 v57, v57
	v_lshlrev_b32_e32 v62, 16, v64
	v_sub_f32_e32 v71, 1.0, v60
	v_add_f32_e32 v60, 1.0, v60
	v_mul_f32_e32 v60, v71, v60
	v_sqrt_f32_e32 v60, v60
	v_add_f32_e32 v57, 1.0, v57
	v_lshlrev_b32_e32 v65, 16, v66
	v_lshlrev_b32_e32 v67, 16, v68
	v_mul_f32_e32 v56, v60, v56
	v_cvt_pk_bf16_f32 v56, v59, v56
	v_add_f32_e32 v59, v108, v61
	v_mul_f32_e32 v59, 0xbfb8aa3b, v59
	v_exp_f32_e32 v59, v59
	ds_read_b32 v58, v93 offset:5232
	v_rcp_f32_e32 v57, v57
	v_mul_f32_e32 v62, 0x3fb8aa3b, v62
	v_add_f32_e32 v59, 1.0, v59
	v_rcp_f32_e32 v59, v59
	v_mul_f32_e32 v65, 0x3fb8aa3b, v65
	v_mul_f32_e32 v67, 0x3fb8aa3b, v67
	v_exp_f32_e32 v62, v62
	v_mul_f32_e32 v59, 0xc1000000, v59
	v_mul_f32_e32 v59, v63, v59
	v_mul_f32_e32 v60, 0x3fb8aa3b, v59
	v_exp_f32_e32 v60, v60
	v_exp_f32_e32 v65, v65
	v_exp_f32_e32 v67, v67
	s_waitcnt lgkmcnt(0)
	v_mul_f32_e32 v57, v57, v58
	v_sub_f32_e32 v61, 1.0, v60
	v_add_f32_e32 v60, 1.0, v60
	v_mul_f32_e32 v60, v61, v60
	v_sqrt_f32_e32 v60, v60
	v_and_b32_e32 v64, 0xffff0000, v64
	v_and_b32_e32 v66, 0xffff0000, v66
	v_and_b32_e32 v68, 0xffff0000, v68
	v_and_b32_e32 v69, 0xffff0000, v70
	v_mul_f32_e32 v57, v60, v57
	s_and_b64 vcc, exec, s[38:39]
	global_store_dword v[74:75], v56, off offset:2112
	v_cvt_pk_bf16_f32 v58, v59, v57
	global_store_dword v[74:75], v58, off offset:3136
	s_cbranch_vccnz .LBB0_515
	v_fma_f32 v57, v67, v69, v68
	v_fma_f32 v57, v65, v57, v66
	v_fma_f32 v57, v62, v57, v64
	s_mov_b64 s[4:5], 0

; template <bool PASS2> ...
;     ...
;             float PA[8], PB[8];
; #pragma unroll
;             for (int e = 0; e < 8; ++e) { PA[e] = __shfl(Ap[e >> 2], (e & 3) * 16 + fr); PB[e] = __shfl(Bp[e >> 2], (e & 3) * 16 + fr); }
;             const size_t si = ((size_t)(b * NCH + c) * 2 + d) * 256 + chn;
;             if (!PASS2) {
;                 float At = 1.f, Bt = 0.f;
; #pragma unroll
;                 for (int e2 = 0; e2 < 8; ++e2) { const int e = d == 0 ? e2 : 7 - e2; Bt = PA[e] * Bt + PB[e]; At *= PA[e]; }
;                 if (fq == 0) { LRA[si] = At; LRB[si] = Bt; }
.LBB0_521:
	v_mul_f32_e32 v54, v61, v54
	v_mul_f32_e32 v55, v55, v66
	v_mul_f32_e32 v64, v54, v55
	v_mul_f32_e32 v54, v62, v65
	v_mul_f32_e32 v55, v67, v60
	v_or_b32_e32 v59, 64, v76
	v_or_b32_e32 v58, 0x80, v76
	v_mul_f32_e32 v60, v54, v55
	ds_bpermute_b32 v68, v76, v60
	ds_bpermute_b32 v54, v76, v57
	ds_bpermute_b32 v71, v59, v60
	ds_bpermute_b32 v55, v59, v57
	ds_bpermute_b32 v70, v58, v60
	ds_bpermute_b32 v56, v58, v57
	ds_bpermute_b32 v69, v77, v60
	ds_bpermute_b32 v57, v77, v57
	ds_bpermute_b32 v66, v76, v64
	ds_bpermute_b32 v63, v76, v72
	ds_bpermute_b32 v67, v59, v64
	ds_bpermute_b32 v62, v59, v72
	ds_bpermute_b32 v65, v58, v64
	ds_bpermute_b32 v61, v58, v72
	ds_bpermute_b32 v64, v77, v64
	ds_bpermute_b32 v60, v77, v72
	s_and_saveexec_b64 s[4:5], s[36:37]
	s_cbranch_execz .LBB0_523
	s_cmp_eq_u32 s64, 1
	s_cselect_b64 vcc, -1, 0
	s_cmp_eq_u32 s64, 2
	s_waitcnt lgkmcnt(0)
	v_cndmask_b32_e32 v78, v68, v71, vcc
	s_cselect_b64 vcc, -1, 0
	s_cmp_eq_u32 s64, 3
	v_cndmask_b32_e32 v78, v78, v70, vcc
	s_cselect_b64 vcc, -1, 0
	s_cmp_eq_u32 s64, 4
	v_cndmask_b32_e32 v78, v78, v69, vcc
	s_cselect_b64 vcc, -1, 0
	s_cmp_eq_u32 s64, 5
	v_cndmask_b32_e32 v78, v78, v66, vcc
	s_cselect_b64 vcc, -1, 0
	s_cmp_eq_u32 s64, 6
	v_cndmask_b32_e32 v78, v78, v67, vcc
	s_cselect_b64 vcc, -1, 0
	s_cmp_eq_u32 s64, 7
	v_cndmask_b32_e32 v78, v78, v65, vcc
	s_cselect_b64 vcc, -1, 0
	s_cmp_eq_u32 s62, 1
	v_cndmask_b32_e32 v78, v78, v64, vcc
	s_cselect_b64 vcc, -1, 0
	s_cmp_eq_u32 s62, 2
	v_cndmask_b32_e32 v79, v68, v71, vcc
	s_cselect_b64 vcc, -1, 0
	s_cmp_eq_u32 s62, 3
	v_cndmask_b32_e32 v79, v79, v70, vcc
	s_cselect_b64 vcc, -1, 0
	s_cmp_eq_u32 s62, 4
	v_cndmask_b32_e32 v79, v79, v69, vcc
	s_cselect_b64 vcc, -1, 0
	s_cmp_eq_u32 s62, 5
	v_cndmask_b32_e32 v79, v79, v66, vcc
	s_cselect_b64 vcc, -1, 0
	s_cmp_eq_u32 s62, 6
	v_cndmask_b32_e32 v79, v79, v67, vcc
	s_cselect_b64 vcc, -1, 0
	s_cmp_eq_u32 s62, 7
	v_cndmask_b32_e32 v79, v79, v65, vcc
	s_cselect_b64 vcc, -1, 0
	s_cmp_eq_u32 s60, 1
	v_cndmask_b32_e32 v79, v79, v64, vcc
	s_cselect_b64 vcc, -1, 0
	s_cmp_eq_u32 s60, 2
	v_cndmask_b32_e32 v81, v68, v71, vcc
	s_cselect_b64 vcc, -1, 0
	s_cmp_eq_u32 s60, 3
	v_cndmask_b32_e32 v81, v81, v70, vcc
	s_cselect_b64 vcc, -1, 0
	s_cmp_eq_u32 s60, 4
	v_cndmask_b32_e32 v81, v81, v69, vcc
	s_cselect_b64 vcc, -1, 0
	s_cmp_eq_u32 s60, 5
	v_cndmask_b32_e32 v81, v81, v66, vcc
	s_cselect_b64 vcc, -1, 0
	s_cmp_eq_u32 s60, 6
	v_cndmask_b32_e32 v81, v81, v67, vcc
	s_cselect_b64 vcc, -1, 0
	s_cmp_eq_u32 s60, 7
	v_cndmask_b32_e32 v81, v81, v65, vcc
	s_cselect_b64 vcc, -1, 0
	s_cmp_eq_u32 s58, 1
	v_cndmask_b32_e32 v81, v81, v64, vcc
	s_cselect_b64 vcc, -1, 0
	s_cmp_eq_u32 s58, 2
	v_cndmask_b32_e32 v82, v68, v71, vcc
	s_cselect_b64 vcc, -1, 0
	s_cmp_eq_u32 s58, 3
	v_cndmask_b32_e32 v82, v82, v70, vcc
	s_cselect_b64 vcc, -1, 0
	s_cmp_eq_u32 s58, 4
	v_cndmask_b32_e32 v82, v82, v69, vcc
	s_cselect_b64 vcc, -1, 0
	s_cmp_eq_u32 s58, 5
	v_cndmask_b32_e32 v82, v82, v66, vcc
	s_cselect_b64 vcc, -1, 0
	s_cmp_eq_u32 s58, 6
	v_cndmask_b32_e32 v82, v82, v67, vcc
	s_cselect_b64 vcc, -1, 0
	s_cmp_eq_u32 s58, 7
	v_cndmask_b32_e32 v82, v82, v65, vcc
	s_cselect_b64 vcc, -1, 0
	s_cmp_eq_u32 s56, 1
	v_cndmask_b32_e32 v82, v82, v64, vcc
	s_cselect_b64 vcc, -1, 0
	s_cmp_eq_u32 s56, 2
	v_cndmask_b32_e32 v83, v68, v71, vcc
	s_cselect_b64 vcc, -1, 0
	s_cmp_eq_u32 s56, 3
	v_cndmask_b32_e32 v83, v83, v70, vcc
	s_cselect_b64 vcc, -1, 0
	s_cmp_eq_u32 s56, 4
	v_cndmask_b32_e32 v83, v83, v69, vcc
	s_cselect_b64 vcc, -1, 0
	s_cmp_eq_u32 s56, 5
	v_cndmask_b32_e32 v83, v83, v66, vcc
	s_cselect_b64 vcc, -1, 0
	s_cmp_eq_u32 s56, 6
	v_cndmask_b32_e32 v83, v83, v67, vcc
	s_cselect_b64 vcc, -1, 0
	s_cmp_eq_u32 s56, 7
	v_cndmask_b32_e32 v83, v83, v65, vcc
	s_cselect_b64 vcc, -1, 0
	s_cmp_eq_u32 s54, 1
	v_cndmask_b32_e32 v83, v83, v64, vcc
	s_cselect_b64 vcc, -1, 0
	s_cmp_eq_u32 s54, 2
	v_cndmask_b32_e32 v84, v68, v71, vcc
	s_cselect_b64 vcc, -1, 0
	s_cmp_eq_u32 s54, 3
	v_cndmask_b32_e32 v84, v84, v70, vcc
	s_cselect_b64 vcc, -1, 0
	s_cmp_eq_u32 s54, 4
	v_cndmask_b32_e32 v84, v84, v69, vcc
	s_cselect_b64 vcc, -1, 0
	s_cmp_eq_u32 s54, 5
	v_cndmask_b32_e32 v84, v84, v66, vcc
	s_cselect_b64 vcc, -1, 0
	s_cmp_eq_u32 s54, 6
	v_cndmask_b32_e32 v84, v84, v67, vcc
	s_cselect_b64 vcc, -1, 0
	s_cmp_eq_u32 s54, 7
	v_cndmask_b32_e32 v84, v84, v65, vcc
	s_cselect_b64 vcc, -1, 0
	s_cmp_eq_u32 s52, 1
	v_cndmask_b32_e32 v84, v84, v64, vcc
	s_cselect_b64 vcc, -1, 0
	s_cmp_eq_u32 s52, 2
	v_cndmask_b32_e32 v85, v68, v71, vcc
	s_cselect_b64 vcc, -1, 0
	s_cmp_eq_u32 s52, 3
	v_cndmask_b32_e32 v85, v85, v70, vcc
	s_cselect_b64 vcc, -1, 0
	s_cmp_eq_u32 s52, 4
	v_cndmask_b32_e32 v85, v85, v69, vcc
	s_cselect_b64 vcc, -1, 0
	s_cmp_eq_u32 s52, 5
	v_cndmask_b32_e32 v85, v85, v66, vcc
	s_cselect_b64 vcc, -1, 0
	s_cmp_eq_u32 s52, 6
	v_cndmask_b32_e32 v85, v85, v67, vcc
	s_cselect_b64 vcc, -1, 0
	s_cmp_eq_u32 s52, 7
	v_cndmask_b32_e32 v85, v85, v65, vcc
	s_cselect_b64 vcc, -1, 0
	s_cmp_eq_u32 s50, 1
	v_cndmask_b32_e32 v85, v85, v64, vcc
	s_cselect_b64 vcc, -1, 0
	s_cmp_eq_u32 s50, 2
	v_cndmask_b32_e32 v68, v68, v71, vcc
	s_cselect_b64 vcc, -1, 0
	s_cmp_eq_u32 s50, 3
	v_cndmask_b32_e32 v68, v68, v70, vcc
	s_cselect_b64 vcc, -1, 0
	s_cmp_eq_u32 s50, 4
	v_cndmask_b32_e32 v68, v68, v69, vcc
	s_cselect_b64 vcc, -1, 0
	s_cmp_eq_u32 s50, 5
	v_cndmask_b32_e32 v66, v68, v66, vcc
	s_cselect_b64 vcc, -1, 0
	s_cmp_eq_u32 s50, 6
	v_cndmask_b32_e32 v66, v66, v67, vcc
	s_cselect_b64 vcc, -1, 0
	v_cndmask_b32_e32 v65, v66, v65, vcc
	v_cndmask_b32_e64 v66, v60, v54, s[48:49]
	v_fmac_f32_e32 v66, 0, v78
	v_cndmask_b32_e64 v67, v61, v55, s[48:49]
	v_fmac_f32_e32 v67, v79, v66
	v_cndmask_b32_e64 v66, v62, v56, s[48:49]
	v_mul_f32_e32 v80, v78, v79
	v_fmac_f32_e32 v66, v81, v67
	v_cndmask_b32_e64 v67, v63, v57, s[48:49]
	v_mul_f32_e32 v80, v81, v80
	v_fmac_f32_e32 v67, v82, v66
	v_cndmask_b32_e64 v57, v57, v63, s[48:49]
	v_mul_f32_e32 v80, v82, v80
	s_cmp_eq_u32 s50, 7
	v_fmac_f32_e32 v57, v83, v67
	v_cndmask_b32_e64 v56, v56, v62, s[48:49]
	v_mul_f32_e32 v80, v83, v80
	s_cselect_b64 vcc, -1, 0
	v_fmac_f32_e32 v56, v84, v57
	v_cndmask_b32_e64 v55, v55, v61, s[48:49]
	v_mov_b32_e32 v73, s67
	v_or_b32_e32 v72, s66, v92
	v_mul_f32_e32 v80, v84, v80
	v_cndmask_b32_e32 v64, v65, v64, vcc
	v_fmac_f32_e32 v55, v85, v56
	v_cndmask_b32_e64 v60, v54, v60, s[48:49]
	v_mul_f32_e32 v80, v85, v80
	v_fmac_f32_e32 v60, v64, v55
	v_lshlrev_b64 v[54:55], 2, v[72:73]
	v_mul_f32_e32 v65, v64, v80
	v_lshl_add_u64 v[56:57], s[44:45], 0, v[54:55]
	v_lshl_add_u64 v[54:55], s[42:43], 0, v[54:55]
	global_store_dword v[54:55], v65, off
	global_store_dword v[56:57], v60, off
; __device__ __forceinline__ unsigned cvt_pk_bf16(float lo, float hi) { unsigned r; asm volatile("v_cvt_pk_bf16_f32 %0, %1, %2" : "=v"(r) : "v"(lo), "v"(hi)); return r; }
; __device__ __forceinline__ float bflo(unsigned w) { return __uint_as_float(w << 16); }
; __device__ __forceinline__ float bfhi(unsigned w) { return __uint_as_float(w & 0xffff0000u); }
; __device__ __forceinline__ float sigm(float x) { return __builtin_amdgcn_rcpf(1.f + __expf(-x)); }
; #define MFMA16(a, b, c) __builtin_amdgcn_mfma_f32_16x16x32_bf16((a), (b), (c), 0, 0, 0)
; template <bool PASS2> ...
;     ...
;                 f32x4 ga[2], gx[2];
;                 ga[0] = ga[1] = gx[0] = gx[1] = (f32x4){0.f, 0.f, 0.f, 0.f};
; #pragma unroll
;                 for (int ks = 0; ks < 2; ++ks) {
; #pragma unroll
;                     for (int tb = 0; tb < 2; ++tb) { ga[tb] = MFMA16(af[tb][ks], wfa[cb][ks], ga[tb]); gx[tb] = MFMA16(af[tb][ks], wfx[cb][ks], gx[tb]); } }
;                 const float ba = pba[cb], bx = pbx[cb], sp = log1pf(__expf(-plm[cb]));
; #pragma unroll
;                 for (int tb = 0; tb < 2; ++tb)
; #pragma unroll
;                     for (int q = 0; q < 4; ++q) { const float xv = xl[(tb * 16 + fq * 4 + q) * 68 + cb * 16 + fr];
;                         const float r = sigm(ga[tb][q] + ba), ig = sigm(gx[tb][q] + bx), la = -8.f * r * sp;
;                         const float aa = __expf(la), om = (1.f - aa) * (1.f + aa), bb = __builtin_amdgcn_sqrtf(om) * (ig * xv);
;                         const unsigned pk = cvt_pk_bf16(la, bb);
;                         labd[(size_t)(tb * 16 + q) * 256 + cb * 16] = pk;
;                         av[tb][q] = __expf(bflo(pk)); bv[tb][q] = bfhi(pk); }
.LBB0_523:
	s_or_b64 exec, exec, s[4:5]
	s_waitcnt lgkmcnt(0)
	v_mfma_f32_16x16x32_bf16 v[54:57], v[2:5], v[46:49], 0
	s_mov_b64 s[4:5], -1
	v_mfma_f32_16x16x32_bf16 v[60:63], v[2:5], v[50:53], 0
	v_mfma_f32_16x16x32_bf16 v[46:49], v[14:17], v[46:49], 0
	v_mfma_f32_16x16x32_bf16 v[64:67], v[14:17], v[50:53], 0
	v_mfma_f32_16x16x32_bf16 v[54:57], v[6:9], v[38:41], v[54:57]
	v_mfma_f32_16x16x32_bf16 v[50:53], v[6:9], v[42:45], v[60:63]
	v_mfma_f32_16x16x32_bf16 v[46:49], v[18:21], v[38:41], v[46:49]
	v_mfma_f32_16x16x32_bf16 v[38:41], v[18:21], v[42:45], v[64:67]
	v_mul_f32_e32 v42, 0xbfb8aa3b, v106
	v_exp_f32_e32 v44, v42
	s_nop 3
	v_add_f32_e32 v51, v104, v51
	v_mul_f32_e32 v51, 0xbfb8aa3b, v51
	v_exp_f32_e32 v51, v51
	v_add_f32_e32 v45, 1.0, v44
	v_add_f32_e32 v42, -1.0, v45
	v_sub_f32_e32 v43, v42, v45
	v_add_f32_e32 v43, 1.0, v43
	v_sub_f32_e32 v42, v44, v42
	v_add_f32_e32 v60, v42, v43
	v_frexp_mant_f32_e32 v42, v45
	v_cmp_gt_f32_e32 vcc, s70, v42
	v_cvt_f64_f32_e32 v[42:43], v45
	v_frexp_exp_i32_f64_e32 v42, v[42:43]
	v_subbrev_co_u32_e32 v42, vcc, 0, v42, vcc
	v_sub_u32_e32 v43, 0, v42
	v_ldexp_f32 v45, v45, v43
	v_ldexp_f32 v43, v60, v43
	v_add_f32_e32 v60, -1.0, v45
	v_add_f32_e32 v61, 1.0, v60
	v_sub_f32_e32 v61, v45, v61
	v_add_f32_e32 v61, v43, v61
	v_add_f32_e32 v62, v60, v61
	v_sub_f32_e32 v60, v62, v60
	v_sub_f32_e32 v60, v61, v60
	v_add_f32_e32 v61, 1.0, v45
	v_add_f32_e32 v63, -1.0, v61
	v_sub_f32_e32 v45, v45, v63
	v_add_f32_e32 v43, v43, v45
	v_add_f32_e32 v45, v61, v43
	v_sub_f32_e32 v61, v45, v61
	v_sub_f32_e32 v43, v43, v61
	v_rcp_f32_e32 v61, v45
	v_cvt_f32_i32_e32 v42, v42
	v_cmp_neq_f32_e32 vcc, s12, v44
	v_add_f32_e32 v51, 1.0, v51
	v_mul_f32_e32 v63, v62, v61
	v_mul_f32_e32 v64, v45, v63
	v_fma_f32 v65, v63, v45, -v64
	v_fmac_f32_e32 v65, v63, v43
	v_add_f32_e32 v66, v64, v65
	v_sub_f32_e32 v67, v62, v66
	v_sub_f32_e32 v62, v62, v67
	v_sub_f32_e32 v64, v66, v64
	v_sub_f32_e32 v62, v62, v66
	v_add_f32_e32 v60, v60, v62
	v_sub_f32_e32 v62, v64, v65
	v_add_f32_e32 v60, v62, v60
	v_add_f32_e32 v62, v67, v60
	v_mul_f32_e32 v64, v61, v62
	v_mul_f32_e32 v65, v45, v64
	v_fma_f32 v45, v64, v45, -v65
	v_fmac_f32_e32 v45, v64, v43
	v_sub_f32_e32 v43, v67, v62
	v_add_f32_e32 v43, v60, v43
	v_add_f32_e32 v60, v65, v45
	v_sub_f32_e32 v66, v62, v60
	v_sub_f32_e32 v62, v62, v66
	v_sub_f32_e32 v65, v60, v65
	v_sub_f32_e32 v60, v62, v60
	v_add_f32_e32 v43, v43, v60
	v_sub_f32_e32 v45, v65, v45
	v_add_f32_e32 v43, v45, v43
	v_add_f32_e32 v45, v63, v64
	v_add_f32_e32 v43, v66, v43
	v_sub_f32_e32 v60, v45, v63
	v_mul_f32_e32 v43, v61, v43
	v_sub_f32_e32 v60, v64, v60
	v_add_f32_e32 v43, v60, v43
	v_mul_f32_e32 v63, 0x3f317218, v42
	v_add_f32_e32 v60, v45, v43
	v_fma_f32 v64, v42, s71, -v63
	v_mul_f32_e32 v61, v60, v60
	v_fmac_f32_e32 v64, 0xb102e308, v42
	v_sub_f32_e32 v42, v60, v45
	v_fmamk_f32 v62, v61, 0x3e9b6dac, v198
	v_sub_f32_e32 v42, v43, v42
	v_add_f32_e32 v43, v63, v64
	v_fmaak_f32 v62, v61, v62, 0x3f2aaada
	v_sub_f32_e32 v45, v43, v63
	v_ldexp_f32 v63, v60, 1
	v_mul_f32_e32 v60, v60, v61
	v_mul_f32_e32 v60, v60, v62
	v_add_f32_e32 v61, v63, v60
	v_sub_f32_e32 v62, v61, v63
	v_ldexp_f32 v42, v42, 1
	v_sub_f32_e32 v60, v60, v62
	v_add_f32_e32 v42, v42, v60
	v_add_f32_e32 v60, v61, v42
	v_sub_f32_e32 v61, v60, v61
	v_sub_f32_e32 v42, v42, v61
	v_add_f32_e32 v61, v43, v60
	v_sub_f32_e32 v62, v61, v43
	v_sub_f32_e32 v63, v61, v62
	v_sub_f32_e32 v45, v64, v45
	v_sub_f32_e32 v43, v43, v63
	v_sub_f32_e32 v60, v60, v62
	v_add_f32_e32 v43, v60, v43
	v_add_f32_e32 v60, v45, v42
	v_sub_f32_e32 v62, v60, v45
	v_sub_f32_e32 v63, v60, v62
	v_sub_f32_e32 v45, v45, v63
	v_sub_f32_e32 v42, v42, v62
	v_add_f32_e32 v43, v60, v43
	v_add_f32_e32 v42, v42, v45
	v_add_f32_e32 v45, v61, v43
	v_sub_f32_e32 v60, v45, v61
	v_sub_f32_e32 v43, v43, v60
	v_add_f32_e32 v42, v42, v43
	v_add_f32_e32 v42, v45, v42
	v_cndmask_b32_e32 v42, v203, v42, vcc
	v_cmp_ngt_f32_e32 vcc, -1.0, v44
	v_add_f32_e32 v45, v104, v50
	v_mul_f32_e32 v45, 0xbfb8aa3b, v45
	v_cndmask_b32_e32 v42, v204, v42, vcc
	v_cmp_neq_f32_e32 vcc, -1.0, v44
	v_exp_f32_e32 v45, v45
	v_rcp_f32_e32 v51, v51
	v_cndmask_b32_e32 v42, v205, v42, vcc
	v_cmp_lt_f32_e64 vcc, |v44|, s13
	v_add_f32_e32 v45, 1.0, v45
	v_rcp_f32_e32 v45, v45
	v_cndmask_b32_e32 v43, v42, v44, vcc
	v_add_f32_e32 v44, v105, v54
	v_mul_f32_e32 v44, 0xbfb8aa3b, v44
	v_exp_f32_e32 v44, v44
	ds_read_b32 v42, v93 offset:128
	v_add_f32_e32 v52, v104, v52
	v_mul_f32_e32 v52, 0xbfb8aa3b, v52
	v_add_f32_e32 v44, 1.0, v44
	v_rcp_f32_e32 v44, v44
	s_waitcnt lgkmcnt(0)
	v_mul_f32_e32 v42, v42, v45
	v_exp_f32_e32 v52, v52
	v_add_f32_e32 v46, v105, v46
	v_mul_f32_e32 v44, 0xc1000000, v44
	v_mul_f32_e32 v44, v43, v44
	v_mul_f32_e32 v50, 0x3fb8aa3b, v44
	v_exp_f32_e32 v50, v50
	v_add_f32_e32 v52, 1.0, v52
	v_rcp_f32_e32 v52, v52
	v_add_f32_e32 v53, v104, v53
	v_sub_f32_e32 v54, 1.0, v50
	v_add_f32_e32 v50, 1.0, v50
	v_mul_f32_e32 v50, v54, v50
	v_sqrt_f32_e32 v50, v50
	v_mul_f32_e32 v46, 0xbfb8aa3b, v46
	v_mul_f32_e32 v53, 0xbfb8aa3b, v53
	v_exp_f32_e32 v46, v46
	v_mul_f32_e32 v42, v42, v50
	v_add_f32_e32 v50, v105, v55
	v_mul_f32_e32 v50, 0xbfb8aa3b, v50
	v_exp_f32_e32 v50, v50
	v_cvt_pk_bf16_f32 v44, v44, v42
	ds_read_b32 v45, v93 offset:400
	global_store_dword v[100:101], v44, off offset:128
	v_add_f32_e32 v50, 1.0, v50
	v_rcp_f32_e32 v50, v50
	v_exp_f32_e32 v53, v53
	s_waitcnt lgkmcnt(0)
; __device__ __forceinline__ unsigned cvt_pk_bf16(float lo, float hi) { unsigned r; asm volatile("v_cvt_pk_bf16_f32 %0, %1, %2" : "=v"(r) : "v"(lo), "v"(hi)); return r; }
; __device__ __forceinline__ float bflo(unsigned w) { return __uint_as_float(w << 16); }
; __device__ __forceinline__ float bfhi(unsigned w) { return __uint_as_float(w & 0xffff0000u); }
; __device__ __forceinline__ float sigm(float x) { return __builtin_amdgcn_rcpf(1.f + __expf(-x)); }
; template <bool PASS2> ...
;     ...
; #pragma unroll
;                 for (int tb = 0; tb < 2; ++tb)
; #pragma unroll
;                     for (int q = 0; q < 4; ++q) { const float xv = xl[(tb * 16 + fq * 4 + q) * 68 + cb * 16 + fr];
;                         const float r = sigm(ga[tb][q] + ba), ig = sigm(gx[tb][q] + bx), la = -8.f * r * sp;
;                         const float aa = __expf(la), om = (1.f - aa) * (1.f + aa), bb = __builtin_amdgcn_sqrtf(om) * (ig * xv);
;                         const unsigned pk = cvt_pk_bf16(la, bb);
;                         labd[(size_t)(tb * 16 + q) * 256 + cb * 16] = pk;
;                         av[tb][q] = __expf(bflo(pk)); bv[tb][q] = bfhi(pk); }
;             } else {
; #pragma unroll
;                 for (int tb = 0; tb < 2; ++tb)
; #pragma unroll
;                     for (int q = 0; q < 4; ++q) { const unsigned pk = pkv[cb][tb][q]; av[tb][q] = __expf(bflo(pk)); bv[tb][q] = bfhi(pk); }
;             }
; #pragma unroll
;             for (int tb = 0; tb < 2; ++tb) {
;                 Ap[tb] = (av[tb][0] * av[tb][1]) * (av[tb][2] * av[tb][3]);
;                 Bp[tb] = d == 0 ? ((bv[tb][0] * av[tb][1] + bv[tb][1]) * av[tb][2] + bv[tb][2]) * av[tb][3] + bv[tb][3]
;                                 : ((bv[tb][3] * av[tb][2] + bv[tb][2]) * av[tb][1] + bv[tb][1]) * av[tb][0] + bv[tb][0];
	v_mul_f32_e32 v45, v51, v45
	v_add_f32_e32 v46, 1.0, v46
	v_mul_f32_e32 v50, 0xc1000000, v50
	v_mul_f32_e32 v50, v43, v50
	v_mul_f32_e32 v54, 0x3fb8aa3b, v50
	v_exp_f32_e32 v54, v54
	v_add_f32_e32 v53, 1.0, v53
	v_rcp_f32_e32 v46, v46
	v_add_f32_e32 v47, v105, v47
	v_sub_f32_e32 v55, 1.0, v54
	v_add_f32_e32 v54, 1.0, v54
	v_mul_f32_e32 v54, v55, v54
	v_sqrt_f32_e32 v54, v54
	v_rcp_f32_e32 v53, v53
	v_mul_f32_e32 v47, 0xbfb8aa3b, v47
	v_add_f32_e32 v38, v104, v38
	v_mul_f32_e32 v45, v45, v54
	v_add_f32_e32 v54, v105, v56
	v_mul_f32_e32 v54, 0xbfb8aa3b, v54
	v_exp_f32_e32 v54, v54
	v_cvt_pk_bf16_f32 v50, v50, v45
	ds_read_b32 v51, v93 offset:672
	global_store_dword v[100:101], v50, off offset:1152
	v_add_f32_e32 v54, 1.0, v54
	v_rcp_f32_e32 v54, v54
	v_exp_f32_e32 v47, v47
	s_waitcnt lgkmcnt(0)
	v_mul_f32_e32 v51, v52, v51
	v_mul_f32_e32 v38, 0xbfb8aa3b, v38
	v_mul_f32_e32 v54, 0xc1000000, v54
	v_mul_f32_e32 v54, v43, v54
	v_mul_f32_e32 v55, 0x3fb8aa3b, v54
	v_exp_f32_e32 v55, v55
	v_exp_f32_e32 v38, v38
	v_mul_f32_e32 v46, 0xc1000000, v46
	v_mul_f32_e32 v46, v43, v46
	v_sub_f32_e32 v56, 1.0, v55
	v_add_f32_e32 v55, 1.0, v55
	v_mul_f32_e32 v55, v56, v55
	v_sqrt_f32_e32 v55, v55
	v_add_f32_e32 v47, 1.0, v47
	v_rcp_f32_e32 v47, v47
	v_add_f32_e32 v38, 1.0, v38
	v_mul_f32_e32 v51, v51, v55
	v_add_f32_e32 v55, v105, v57
	v_mul_f32_e32 v55, 0xbfb8aa3b, v55
	v_exp_f32_e32 v55, v55
	v_cvt_pk_bf16_f32 v52, v54, v51
	ds_read_b32 v54, v93 offset:944
	global_store_dword v[100:101], v52, off offset:2176
	v_add_f32_e32 v55, 1.0, v55
	v_rcp_f32_e32 v55, v55
	v_rcp_f32_e32 v38, v38
	s_waitcnt lgkmcnt(0)
	v_mul_f32_e32 v53, v53, v54
	v_mul_f32_e32 v47, 0xc1000000, v47
	v_mul_f32_e32 v55, 0xc1000000, v55
	v_mul_f32_e32 v55, v43, v55
	v_mul_f32_e32 v56, 0x3fb8aa3b, v55
	v_exp_f32_e32 v56, v56
	v_add_f32_e32 v39, v104, v39
	v_mul_f32_e32 v47, v43, v47
	v_mul_f32_e32 v39, 0xbfb8aa3b, v39
	v_sub_f32_e32 v57, 1.0, v56
	v_add_f32_e32 v56, 1.0, v56
	v_mul_f32_e32 v56, v57, v56
	v_sqrt_f32_e32 v56, v56
	v_exp_f32_e32 v39, v39
	v_add_f32_e32 v40, v104, v40
	v_mul_f32_e32 v40, 0xbfb8aa3b, v40
	v_mul_f32_e32 v53, v56, v53
	v_mul_f32_e32 v56, 0x3fb8aa3b, v46
	v_exp_f32_e32 v56, v56
	v_cvt_pk_bf16_f32 v54, v55, v53
	ds_read_b32 v55, v93 offset:4480
	global_store_dword v[100:101], v54, off offset:3200
	v_sub_f32_e32 v57, 1.0, v56
	v_add_f32_e32 v56, 1.0, v56
	v_mul_f32_e32 v56, v57, v56
	v_sqrt_f32_e32 v56, v56
	s_waitcnt lgkmcnt(0)
	v_mul_f32_e32 v38, v38, v55
	v_mul_f32_e32 v55, 0x3fb8aa3b, v47
	v_exp_f32_e32 v55, v55
	v_mul_f32_e32 v38, v56, v38
	v_cvt_pk_bf16_f32 v38, v46, v38
	ds_read_b32 v46, v93 offset:4752
	v_add_f32_e32 v39, 1.0, v39
	v_sub_f32_e32 v56, 1.0, v55
	v_add_f32_e32 v55, 1.0, v55
	v_rcp_f32_e32 v39, v39
	v_mul_f32_e32 v55, v56, v55
	v_sqrt_f32_e32 v55, v55
	global_store_dword v[74:75], v38, off offset:128
	s_waitcnt lgkmcnt(0)
	v_mul_f32_e32 v39, v39, v46
	v_exp_f32_e32 v40, v40
	v_mul_f32_e32 v39, v55, v39
	v_cvt_pk_bf16_f32 v39, v47, v39
	v_add_f32_e32 v47, v105, v48
	v_mul_f32_e32 v47, 0xbfb8aa3b, v47
	v_exp_f32_e32 v47, v47
	ds_read_b32 v46, v93 offset:5024
	v_add_f32_e32 v40, 1.0, v40
	v_rcp_f32_e32 v40, v40
	v_add_f32_e32 v47, 1.0, v47
	v_rcp_f32_e32 v47, v47
	global_store_dword v[74:75], v39, off offset:1152
	s_waitcnt lgkmcnt(0)
	v_mul_f32_e32 v40, v40, v46
	v_add_f32_e32 v41, v104, v41
	v_mul_f32_e32 v47, 0xc1000000, v47
	v_mul_f32_e32 v47, v43, v47
	v_mul_f32_e32 v48, 0x3fb8aa3b, v47
	v_exp_f32_e32 v48, v48
	v_mul_f32_e32 v41, 0xbfb8aa3b, v41
	v_exp_f32_e32 v41, v41
	v_lshlrev_b32_e32 v42, 16, v44
	v_sub_f32_e32 v55, 1.0, v48
	v_add_f32_e32 v48, 1.0, v48
	v_mul_f32_e32 v48, v55, v48
	v_sqrt_f32_e32 v48, v48
	v_add_f32_e32 v41, 1.0, v41
	v_lshlrev_b32_e32 v45, 16, v50
	v_lshlrev_b32_e32 v51, 16, v52
	v_mul_f32_e32 v40, v48, v40
	v_cvt_pk_bf16_f32 v40, v47, v40
	v_add_f32_e32 v47, v105, v49
	v_mul_f32_e32 v47, 0xbfb8aa3b, v47
	v_exp_f32_e32 v47, v47
	ds_read_b32 v46, v93 offset:5296
	v_rcp_f32_e32 v41, v41
	v_mul_f32_e32 v42, 0x3fb8aa3b, v42
	v_add_f32_e32 v47, 1.0, v47
	v_rcp_f32_e32 v47, v47
	v_mul_f32_e32 v45, 0x3fb8aa3b, v45
	v_mul_f32_e32 v51, 0x3fb8aa3b, v51
	v_exp_f32_e32 v42, v42
	v_mul_f32_e32 v47, 0xc1000000, v47
	v_mul_f32_e32 v43, v43, v47
	v_mul_f32_e32 v47, 0x3fb8aa3b, v43
	v_exp_f32_e32 v47, v47
	v_exp_f32_e32 v45, v45
	v_exp_f32_e32 v51, v51
	s_waitcnt lgkmcnt(0)
	v_mul_f32_e32 v41, v41, v46
	v_sub_f32_e32 v48, 1.0, v47
	v_add_f32_e32 v47, 1.0, v47
	v_mul_f32_e32 v47, v48, v47
	v_sqrt_f32_e32 v47, v47
	v_and_b32_e32 v44, 0xffff0000, v44
	v_and_b32_e32 v50, 0xffff0000, v50
	v_and_b32_e32 v52, 0xffff0000, v52
	v_and_b32_e32 v53, 0xffff0000, v54
	v_mul_f32_e32 v41, v47, v41
	s_and_b64 vcc, exec, s[38:39]
	global_store_dword v[74:75], v40, off offset:2176
	v_cvt_pk_bf16_f32 v43, v43, v41
	global_store_dword v[74:75], v43, off offset:3200
	s_cbranch_vccnz .LBB0_525
	v_fma_f32 v41, v51, v53, v52
	v_fma_f32 v41, v45, v41, v50
	v_fma_f32 v41, v42, v41, v44
	s_mov_b64 s[4:5], 0

; template <bool PASS2> ...
;     ...
;             float PA[8], PB[8];
; #pragma unroll
;             for (int e = 0; e < 8; ++e) { PA[e] = __shfl(Ap[e >> 2], (e & 3) * 16 + fr); PB[e] = __shfl(Bp[e >> 2], (e & 3) * 16 + fr); }
;             const size_t si = ((size_t)(b * NCH + c) * 2 + d) * 256 + chn;
;             if (!PASS2) {
;                 float At = 1.f, Bt = 0.f;
; #pragma unroll
;                 for (int e2 = 0; e2 < 8; ++e2) { const int e = d == 0 ? e2 : 7 - e2; Bt = PA[e] * Bt + PB[e]; At *= PA[e]; }
;                 if (fq == 0) { LRA[si] = At; LRB[si] = Bt; }
.LBB0_531:
	v_mul_f32_e32 v38, v44, v38
	v_mul_f32_e32 v39, v39, v43
	v_mul_f32_e32 v55, v38, v39
	v_mul_f32_e32 v38, v42, v45
	v_mul_f32_e32 v39, v51, v46
	v_mul_f32_e32 v42, v38, v39
	ds_bpermute_b32 v50, v76, v42
	ds_bpermute_b32 v38, v76, v41
	ds_bpermute_b32 v53, v59, v42
	ds_bpermute_b32 v39, v59, v41
	ds_bpermute_b32 v52, v58, v42
	ds_bpermute_b32 v40, v58, v41
	ds_bpermute_b32 v51, v77, v42
	ds_bpermute_b32 v41, v77, v41
	ds_bpermute_b32 v48, v76, v55
	ds_bpermute_b32 v45, v76, v54
	ds_bpermute_b32 v49, v59, v55
	ds_bpermute_b32 v44, v59, v54
	ds_bpermute_b32 v47, v58, v55
	ds_bpermute_b32 v43, v58, v54
	ds_bpermute_b32 v46, v77, v55
	ds_bpermute_b32 v42, v77, v54
	s_and_saveexec_b64 s[4:5], s[36:37]
	s_cbranch_execz .LBB0_533
	s_cmp_eq_u32 s64, 1
	s_cselect_b64 vcc, -1, 0
	s_cmp_eq_u32 s64, 2
	s_waitcnt lgkmcnt(0)
	v_cndmask_b32_e32 v56, v50, v53, vcc
	s_cselect_b64 vcc, -1, 0
	s_cmp_eq_u32 s64, 3
	v_cndmask_b32_e32 v56, v56, v52, vcc
	s_cselect_b64 vcc, -1, 0
	s_cmp_eq_u32 s64, 4
	v_cndmask_b32_e32 v56, v56, v51, vcc
	s_cselect_b64 vcc, -1, 0
	s_cmp_eq_u32 s64, 5
	v_cndmask_b32_e32 v56, v56, v48, vcc
	s_cselect_b64 vcc, -1, 0
	s_cmp_eq_u32 s64, 6
	v_cndmask_b32_e32 v56, v56, v49, vcc
	s_cselect_b64 vcc, -1, 0
	s_cmp_eq_u32 s64, 7
	v_cndmask_b32_e32 v56, v56, v47, vcc
	s_cselect_b64 vcc, -1, 0
	s_cmp_eq_u32 s62, 1
	v_cndmask_b32_e32 v56, v56, v46, vcc
	s_cselect_b64 vcc, -1, 0
	s_cmp_eq_u32 s62, 2
	v_cndmask_b32_e32 v57, v50, v53, vcc
	s_cselect_b64 vcc, -1, 0
	s_cmp_eq_u32 s62, 3
	v_cndmask_b32_e32 v57, v57, v52, vcc
	s_cselect_b64 vcc, -1, 0
	s_cmp_eq_u32 s62, 4
	v_cndmask_b32_e32 v57, v57, v51, vcc
	s_cselect_b64 vcc, -1, 0
	s_cmp_eq_u32 s62, 5
	v_cndmask_b32_e32 v57, v57, v48, vcc
	s_cselect_b64 vcc, -1, 0
	s_cmp_eq_u32 s62, 6
	v_cndmask_b32_e32 v57, v57, v49, vcc
	s_cselect_b64 vcc, -1, 0
	s_cmp_eq_u32 s62, 7
	v_cndmask_b32_e32 v57, v57, v47, vcc
	s_cselect_b64 vcc, -1, 0
	s_cmp_eq_u32 s60, 1
	v_cndmask_b32_e32 v57, v57, v46, vcc
	s_cselect_b64 vcc, -1, 0
	s_cmp_eq_u32 s60, 2
	v_cndmask_b32_e32 v61, v50, v53, vcc
	s_cselect_b64 vcc, -1, 0
	s_cmp_eq_u32 s60, 3
	v_cndmask_b32_e32 v61, v61, v52, vcc
	s_cselect_b64 vcc, -1, 0
	s_cmp_eq_u32 s60, 4
	v_cndmask_b32_e32 v61, v61, v51, vcc
	s_cselect_b64 vcc, -1, 0
	s_cmp_eq_u32 s60, 5
	v_cndmask_b32_e32 v61, v61, v48, vcc
	s_cselect_b64 vcc, -1, 0
	s_cmp_eq_u32 s60, 6
	v_cndmask_b32_e32 v61, v61, v49, vcc
	s_cselect_b64 vcc, -1, 0
	s_cmp_eq_u32 s60, 7
	v_cndmask_b32_e32 v61, v61, v47, vcc
	s_cselect_b64 vcc, -1, 0
	s_cmp_eq_u32 s58, 1
	v_cndmask_b32_e32 v61, v61, v46, vcc
	s_cselect_b64 vcc, -1, 0
	s_cmp_eq_u32 s58, 2
	v_cndmask_b32_e32 v62, v50, v53, vcc
	s_cselect_b64 vcc, -1, 0
	s_cmp_eq_u32 s58, 3
	v_cndmask_b32_e32 v62, v62, v52, vcc
	s_cselect_b64 vcc, -1, 0
	s_cmp_eq_u32 s58, 4
	v_cndmask_b32_e32 v62, v62, v51, vcc
	s_cselect_b64 vcc, -1, 0
	s_cmp_eq_u32 s58, 5
	v_cndmask_b32_e32 v62, v62, v48, vcc
	s_cselect_b64 vcc, -1, 0
	s_cmp_eq_u32 s58, 6
	v_cndmask_b32_e32 v62, v62, v49, vcc
	s_cselect_b64 vcc, -1, 0
	s_cmp_eq_u32 s58, 7
	v_cndmask_b32_e32 v62, v62, v47, vcc
	s_cselect_b64 vcc, -1, 0
	s_cmp_eq_u32 s56, 1
	v_cndmask_b32_e32 v62, v62, v46, vcc
	s_cselect_b64 vcc, -1, 0
	s_cmp_eq_u32 s56, 2
	v_cndmask_b32_e32 v63, v50, v53, vcc
	s_cselect_b64 vcc, -1, 0
	s_cmp_eq_u32 s56, 3
	v_cndmask_b32_e32 v63, v63, v52, vcc
	s_cselect_b64 vcc, -1, 0
	s_cmp_eq_u32 s56, 4
	v_cndmask_b32_e32 v63, v63, v51, vcc
	s_cselect_b64 vcc, -1, 0
	s_cmp_eq_u32 s56, 5
	v_cndmask_b32_e32 v63, v63, v48, vcc
	s_cselect_b64 vcc, -1, 0
	s_cmp_eq_u32 s56, 6
	v_cndmask_b32_e32 v63, v63, v49, vcc
	s_cselect_b64 vcc, -1, 0
	s_cmp_eq_u32 s56, 7
	v_cndmask_b32_e32 v63, v63, v47, vcc
	s_cselect_b64 vcc, -1, 0
	s_cmp_eq_u32 s54, 1
	v_cndmask_b32_e32 v63, v63, v46, vcc
	s_cselect_b64 vcc, -1, 0
	s_cmp_eq_u32 s54, 2
	v_cndmask_b32_e32 v64, v50, v53, vcc
	s_cselect_b64 vcc, -1, 0
	s_cmp_eq_u32 s54, 3
	v_cndmask_b32_e32 v64, v64, v52, vcc
	s_cselect_b64 vcc, -1, 0
	s_cmp_eq_u32 s54, 4
	v_cndmask_b32_e32 v64, v64, v51, vcc
	s_cselect_b64 vcc, -1, 0
	s_cmp_eq_u32 s54, 5
	v_cndmask_b32_e32 v64, v64, v48, vcc
	s_cselect_b64 vcc, -1, 0
	s_cmp_eq_u32 s54, 6
	v_cndmask_b32_e32 v64, v64, v49, vcc
	s_cselect_b64 vcc, -1, 0
	s_cmp_eq_u32 s54, 7
	v_cndmask_b32_e32 v64, v64, v47, vcc
	s_cselect_b64 vcc, -1, 0
	s_cmp_eq_u32 s52, 1
	v_cndmask_b32_e32 v64, v64, v46, vcc
	s_cselect_b64 vcc, -1, 0
	s_cmp_eq_u32 s52, 2
	v_cndmask_b32_e32 v65, v50, v53, vcc
	s_cselect_b64 vcc, -1, 0
	s_cmp_eq_u32 s52, 3
	v_cndmask_b32_e32 v65, v65, v52, vcc
	s_cselect_b64 vcc, -1, 0
	s_cmp_eq_u32 s52, 4
	v_cndmask_b32_e32 v65, v65, v51, vcc
	s_cselect_b64 vcc, -1, 0
	s_cmp_eq_u32 s52, 5
	v_cndmask_b32_e32 v65, v65, v48, vcc
	s_cselect_b64 vcc, -1, 0
	s_cmp_eq_u32 s52, 6
	v_cndmask_b32_e32 v65, v65, v49, vcc
	s_cselect_b64 vcc, -1, 0
	s_cmp_eq_u32 s52, 7
	v_cndmask_b32_e32 v65, v65, v47, vcc
	s_cselect_b64 vcc, -1, 0
	s_cmp_eq_u32 s50, 1
	v_cndmask_b32_e32 v65, v65, v46, vcc
	s_cselect_b64 vcc, -1, 0
	s_cmp_eq_u32 s50, 2
	v_cndmask_b32_e32 v50, v50, v53, vcc
	s_cselect_b64 vcc, -1, 0
	s_cmp_eq_u32 s50, 3
	v_cndmask_b32_e32 v50, v50, v52, vcc
	s_cselect_b64 vcc, -1, 0
	s_cmp_eq_u32 s50, 4
	v_cndmask_b32_e32 v50, v50, v51, vcc
	s_cselect_b64 vcc, -1, 0
	s_cmp_eq_u32 s50, 5
	v_cndmask_b32_e32 v48, v50, v48, vcc
	s_cselect_b64 vcc, -1, 0
	s_cmp_eq_u32 s50, 6
	v_cndmask_b32_e32 v48, v48, v49, vcc
	s_cselect_b64 vcc, -1, 0
	v_cndmask_b32_e32 v47, v48, v47, vcc
	v_cndmask_b32_e64 v48, v42, v38, s[48:49]
	v_fmac_f32_e32 v48, 0, v56
	v_cndmask_b32_e64 v49, v43, v39, s[48:49]
	v_fmac_f32_e32 v49, v57, v48
	v_cndmask_b32_e64 v48, v44, v40, s[48:49]
	v_mul_f32_e32 v60, v56, v57
	v_fmac_f32_e32 v48, v61, v49
	v_cndmask_b32_e64 v49, v45, v41, s[48:49]
	v_mul_f32_e32 v60, v61, v60
	v_fmac_f32_e32 v49, v62, v48
	v_cndmask_b32_e64 v41, v41, v45, s[48:49]
	v_mul_f32_e32 v60, v62, v60
	s_cmp_eq_u32 s50, 7
	v_fmac_f32_e32 v41, v63, v49
	v_cndmask_b32_e64 v40, v40, v44, s[48:49]
	v_mul_f32_e32 v60, v63, v60
	s_cselect_b64 vcc, -1, 0
	v_fmac_f32_e32 v40, v64, v41
	v_cndmask_b32_e64 v39, v39, v43, s[48:49]
	v_mov_b32_e32 v55, s67
	v_or_b32_e32 v54, s66, v94
	v_mul_f32_e32 v60, v64, v60
	v_cndmask_b32_e32 v46, v47, v46, vcc
	v_fmac_f32_e32 v39, v65, v40
	v_cndmask_b32_e64 v42, v38, v42, s[48:49]
	v_mul_f32_e32 v60, v65, v60
	v_fmac_f32_e32 v42, v46, v39
	v_lshlrev_b64 v[38:39], 2, v[54:55]
	v_mul_f32_e32 v47, v46, v60
	v_lshl_add_u64 v[40:41], s[44:45], 0, v[38:39]
	v_lshl_add_u64 v[38:39], s[42:43], 0, v[38:39]
	global_store_dword v[38:39], v47, off
	global_store_dword v[40:41], v42, off
; __device__ __forceinline__ unsigned cvt_pk_bf16(float lo, float hi) { unsigned r; asm volatile("v_cvt_pk_bf16_f32 %0, %1, %2" : "=v"(r) : "v"(lo), "v"(hi)); return r; }
; __device__ __forceinline__ float bflo(unsigned w) { return __uint_as_float(w << 16); }
; __device__ __forceinline__ float bfhi(unsigned w) { return __uint_as_float(w & 0xffff0000u); }
; __device__ __forceinline__ float sigm(float x) { return __builtin_amdgcn_rcpf(1.f + __expf(-x)); }
; #define MFMA16(a, b, c) __builtin_amdgcn_mfma_f32_16x16x32_bf16((a), (b), (c), 0, 0, 0)
; template <bool PASS2> ...
;     ...
;                 f32x4 ga[2], gx[2];
;                 ga[0] = ga[1] = gx[0] = gx[1] = (f32x4){0.f, 0.f, 0.f, 0.f};
; #pragma unroll
;                 for (int ks = 0; ks < 2; ++ks) {
; #pragma unroll
;                     for (int tb = 0; tb < 2; ++tb) { ga[tb] = MFMA16(af[tb][ks], wfa[cb][ks], ga[tb]); gx[tb] = MFMA16(af[tb][ks], wfx[cb][ks], gx[tb]); } }
;                 const float ba = pba[cb], bx = pbx[cb], sp = log1pf(__expf(-plm[cb]));
; #pragma unroll
;                 for (int tb = 0; tb < 2; ++tb)
; #pragma unroll
;                     for (int q = 0; q < 4; ++q) { const float xv = xl[(tb * 16 + fq * 4 + q) * 68 + cb * 16 + fr];
;                         const float r = sigm(ga[tb][q] + ba), ig = sigm(gx[tb][q] + bx), la = -8.f * r * sp;
;                         const float aa = __expf(la), om = (1.f - aa) * (1.f + aa), bb = __builtin_amdgcn_sqrtf(om) * (ig * xv);
;                         const unsigned pk = cvt_pk_bf16(la, bb);
;                         labd[(size_t)(tb * 16 + q) * 256 + cb * 16] = pk;
;                         av[tb][q] = __expf(bflo(pk)); bv[tb][q] = bfhi(pk); }
.LBB0_533:
	s_or_b64 exec, exec, s[4:5]
	s_waitcnt lgkmcnt(0)
	v_mfma_f32_16x16x32_bf16 v[38:41], v[2:5], v[30:33], 0
	s_mov_b64 s[4:5], -1
	v_mfma_f32_16x16x32_bf16 v[42:45], v[2:5], v[34:37], 0
	v_mfma_f32_16x16x32_bf16 v[30:33], v[14:17], v[30:33], 0
	v_mfma_f32_16x16x32_bf16 v[46:49], v[14:17], v[34:37], 0
	v_mfma_f32_16x16x32_bf16 v[38:41], v[6:9], v[22:25], v[38:41]
	v_mfma_f32_16x16x32_bf16 v[34:37], v[6:9], v[26:29], v[42:45]
	v_mfma_f32_16x16x32_bf16 v[30:33], v[18:21], v[22:25], v[30:33]
	v_mfma_f32_16x16x32_bf16 v[22:25], v[18:21], v[26:29], v[46:49]
	v_mul_f32_e32 v26, 0xbfb8aa3b, v103
	v_exp_f32_e32 v28, v26
	s_nop 3
	v_add_f32_e32 v35, v0, v35
	v_mul_f32_e32 v35, 0xbfb8aa3b, v35
	v_exp_f32_e32 v35, v35
	v_add_f32_e32 v29, 1.0, v28
	v_add_f32_e32 v26, -1.0, v29
	v_sub_f32_e32 v27, v26, v29
	v_add_f32_e32 v27, 1.0, v27
	v_sub_f32_e32 v26, v28, v26
	v_add_f32_e32 v42, v26, v27
	v_frexp_mant_f32_e32 v26, v29
	v_cmp_gt_f32_e32 vcc, s70, v26
	v_cvt_f64_f32_e32 v[26:27], v29
	v_frexp_exp_i32_f64_e32 v26, v[26:27]
	v_subbrev_co_u32_e32 v26, vcc, 0, v26, vcc
	v_sub_u32_e32 v27, 0, v26
	v_ldexp_f32 v29, v29, v27
	v_ldexp_f32 v27, v42, v27
	v_add_f32_e32 v42, -1.0, v29
	v_add_f32_e32 v43, 1.0, v42
	v_sub_f32_e32 v43, v29, v43
	v_add_f32_e32 v43, v27, v43
	v_add_f32_e32 v44, v42, v43
	v_sub_f32_e32 v42, v44, v42
	v_sub_f32_e32 v42, v43, v42
	v_add_f32_e32 v43, 1.0, v29
	v_add_f32_e32 v45, -1.0, v43
	v_sub_f32_e32 v29, v29, v45
	v_add_f32_e32 v27, v27, v29
	v_add_f32_e32 v29, v43, v27
	v_sub_f32_e32 v43, v29, v43
	v_sub_f32_e32 v27, v27, v43
	v_rcp_f32_e32 v43, v29
	v_cvt_f32_i32_e32 v26, v26
	v_cmp_neq_f32_e32 vcc, s12, v28
	v_add_f32_e32 v35, 1.0, v35
	v_mul_f32_e32 v45, v44, v43
	v_mul_f32_e32 v46, v29, v45
	v_fma_f32 v47, v45, v29, -v46
	v_fmac_f32_e32 v47, v45, v27
	v_add_f32_e32 v48, v46, v47
	v_sub_f32_e32 v49, v44, v48
	v_sub_f32_e32 v44, v44, v49
	v_sub_f32_e32 v46, v48, v46
	v_sub_f32_e32 v44, v44, v48
	v_add_f32_e32 v42, v42, v44
	v_sub_f32_e32 v44, v46, v47
	v_add_f32_e32 v42, v44, v42
	v_add_f32_e32 v44, v49, v42
	v_mul_f32_e32 v46, v43, v44
	v_mul_f32_e32 v47, v29, v46
	v_fma_f32 v29, v46, v29, -v47
	v_fmac_f32_e32 v29, v46, v27
	v_sub_f32_e32 v27, v49, v44
	v_add_f32_e32 v27, v42, v27
	v_add_f32_e32 v42, v47, v29
	v_sub_f32_e32 v48, v44, v42
	v_sub_f32_e32 v44, v44, v48
	v_sub_f32_e32 v47, v42, v47
	v_sub_f32_e32 v42, v44, v42
	v_add_f32_e32 v27, v27, v42
	v_sub_f32_e32 v29, v47, v29
	v_add_f32_e32 v27, v29, v27
	v_add_f32_e32 v29, v45, v46
	v_add_f32_e32 v27, v48, v27
	v_sub_f32_e32 v42, v29, v45
	v_mul_f32_e32 v27, v43, v27
	v_sub_f32_e32 v42, v46, v42
	v_add_f32_e32 v27, v42, v27
	v_mul_f32_e32 v45, 0x3f317218, v26
	v_add_f32_e32 v42, v29, v27
	v_fma_f32 v46, v26, s71, -v45
	v_mul_f32_e32 v43, v42, v42
	v_fmac_f32_e32 v46, 0xb102e308, v26
	v_sub_f32_e32 v26, v42, v29
	v_fmamk_f32 v44, v43, 0x3e9b6dac, v198
	v_sub_f32_e32 v26, v27, v26
	v_add_f32_e32 v27, v45, v46
	v_fmaak_f32 v44, v43, v44, 0x3f2aaada
	v_sub_f32_e32 v29, v27, v45
	v_ldexp_f32 v45, v42, 1
	v_mul_f32_e32 v42, v42, v43
	v_mul_f32_e32 v42, v42, v44
	v_add_f32_e32 v43, v45, v42
	v_sub_f32_e32 v44, v43, v45
	v_ldexp_f32 v26, v26, 1
	v_sub_f32_e32 v42, v42, v44
	v_add_f32_e32 v26, v26, v42
	v_add_f32_e32 v42, v43, v26
	v_sub_f32_e32 v43, v42, v43
	v_sub_f32_e32 v26, v26, v43
	v_add_f32_e32 v43, v27, v42
	v_sub_f32_e32 v44, v43, v27
	v_sub_f32_e32 v45, v43, v44
	v_sub_f32_e32 v29, v46, v29
	v_sub_f32_e32 v27, v27, v45
	v_sub_f32_e32 v42, v42, v44
	v_add_f32_e32 v27, v42, v27
	v_add_f32_e32 v42, v29, v26
	v_sub_f32_e32 v44, v42, v29
	v_sub_f32_e32 v45, v42, v44
	v_sub_f32_e32 v29, v29, v45
	v_sub_f32_e32 v26, v26, v44
	v_add_f32_e32 v27, v42, v27
	v_add_f32_e32 v26, v26, v29
	v_add_f32_e32 v29, v43, v27
	v_sub_f32_e32 v42, v29, v43
	v_sub_f32_e32 v27, v27, v42
	v_add_f32_e32 v26, v26, v27
	v_add_f32_e32 v26, v29, v26
	v_cndmask_b32_e32 v26, v203, v26, vcc
	v_cmp_ngt_f32_e32 vcc, -1.0, v28
	v_add_f32_e32 v29, v0, v34
	v_mul_f32_e32 v29, 0xbfb8aa3b, v29
	v_cndmask_b32_e32 v26, v204, v26, vcc
	v_cmp_neq_f32_e32 vcc, -1.0, v28
	v_exp_f32_e32 v29, v29
	v_rcp_f32_e32 v35, v35
	v_cndmask_b32_e32 v26, v205, v26, vcc
	v_cmp_lt_f32_e64 vcc, |v28|, s13
	v_add_f32_e32 v29, 1.0, v29
	v_rcp_f32_e32 v29, v29
	v_cndmask_b32_e32 v27, v26, v28, vcc
	v_add_f32_e32 v28, v102, v38
	v_mul_f32_e32 v28, 0xbfb8aa3b, v28
	v_exp_f32_e32 v28, v28
	ds_read_b32 v26, v93 offset:192
	v_add_f32_e32 v36, v0, v36
	v_mul_f32_e32 v36, 0xbfb8aa3b, v36
	v_add_f32_e32 v28, 1.0, v28
	v_rcp_f32_e32 v28, v28
	s_waitcnt lgkmcnt(0)
	v_mul_f32_e32 v26, v26, v29
	v_exp_f32_e32 v36, v36
	v_add_f32_e32 v30, v102, v30
	v_mul_f32_e32 v28, 0xc1000000, v28
	v_mul_f32_e32 v28, v27, v28
	v_mul_f32_e32 v34, 0x3fb8aa3b, v28
	v_exp_f32_e32 v34, v34
	v_add_f32_e32 v36, 1.0, v36
	v_rcp_f32_e32 v36, v36
	v_add_f32_e32 v37, v0, v37
	v_sub_f32_e32 v38, 1.0, v34
	v_add_f32_e32 v34, 1.0, v34
	v_mul_f32_e32 v34, v38, v34
	v_sqrt_f32_e32 v34, v34
	v_mul_f32_e32 v30, 0xbfb8aa3b, v30
	v_mul_f32_e32 v37, 0xbfb8aa3b, v37
	v_exp_f32_e32 v30, v30
	v_mul_f32_e32 v26, v26, v34
	v_add_f32_e32 v34, v102, v39
	v_mul_f32_e32 v34, 0xbfb8aa3b, v34
	v_exp_f32_e32 v34, v34
	v_cvt_pk_bf16_f32 v28, v28, v26
	ds_read_b32 v29, v93 offset:464
	global_store_dword v[100:101], v28, off offset:192
	v_add_f32_e32 v34, 1.0, v34
	v_rcp_f32_e32 v34, v34
	v_exp_f32_e32 v37, v37
	s_waitcnt lgkmcnt(0)
; __device__ __forceinline__ unsigned cvt_pk_bf16(float lo, float hi) { unsigned r; asm volatile("v_cvt_pk_bf16_f32 %0, %1, %2" : "=v"(r) : "v"(lo), "v"(hi)); return r; }
; __device__ __forceinline__ float bflo(unsigned w) { return __uint_as_float(w << 16); }
; __device__ __forceinline__ float bfhi(unsigned w) { return __uint_as_float(w & 0xffff0000u); }
; __device__ __forceinline__ float sigm(float x) { return __builtin_amdgcn_rcpf(1.f + __expf(-x)); }
; template <bool PASS2> ...
;     ...
; #pragma unroll
;                 for (int tb = 0; tb < 2; ++tb)
; #pragma unroll
;                     for (int q = 0; q < 4; ++q) { const float xv = xl[(tb * 16 + fq * 4 + q) * 68 + cb * 16 + fr];
;                         const float r = sigm(ga[tb][q] + ba), ig = sigm(gx[tb][q] + bx), la = -8.f * r * sp;
;                         const float aa = __expf(la), om = (1.f - aa) * (1.f + aa), bb = __builtin_amdgcn_sqrtf(om) * (ig * xv);
;                         const unsigned pk = cvt_pk_bf16(la, bb);
;                         labd[(size_t)(tb * 16 + q) * 256 + cb * 16] = pk;
;                         av[tb][q] = __expf(bflo(pk)); bv[tb][q] = bfhi(pk); }
;             } else {
; #pragma unroll
;                 for (int tb = 0; tb < 2; ++tb)
; #pragma unroll
;                     for (int q = 0; q < 4; ++q) { const unsigned pk = pkv[cb][tb][q]; av[tb][q] = __expf(bflo(pk)); bv[tb][q] = bfhi(pk); }
;             }
; #pragma unroll
;             for (int tb = 0; tb < 2; ++tb) {
;                 Ap[tb] = (av[tb][0] * av[tb][1]) * (av[tb][2] * av[tb][3]);
;                 Bp[tb] = d == 0 ? ((bv[tb][0] * av[tb][1] + bv[tb][1]) * av[tb][2] + bv[tb][2]) * av[tb][3] + bv[tb][3]
;                                 : ((bv[tb][3] * av[tb][2] + bv[tb][2]) * av[tb][1] + bv[tb][1]) * av[tb][0] + bv[tb][0];
	v_mul_f32_e32 v29, v35, v29
	v_add_f32_e32 v30, 1.0, v30
	v_mul_f32_e32 v34, 0xc1000000, v34
	v_mul_f32_e32 v34, v27, v34
	v_mul_f32_e32 v38, 0x3fb8aa3b, v34
	v_exp_f32_e32 v38, v38
	v_add_f32_e32 v37, 1.0, v37
	v_rcp_f32_e32 v30, v30
	v_add_f32_e32 v31, v102, v31
	v_sub_f32_e32 v39, 1.0, v38
	v_add_f32_e32 v38, 1.0, v38
	v_mul_f32_e32 v38, v39, v38
	v_sqrt_f32_e32 v38, v38
	v_rcp_f32_e32 v37, v37
	v_mul_f32_e32 v31, 0xbfb8aa3b, v31
	v_add_f32_e32 v22, v0, v22
	v_mul_f32_e32 v29, v29, v38
	v_add_f32_e32 v38, v102, v40
	v_mul_f32_e32 v38, 0xbfb8aa3b, v38
	v_exp_f32_e32 v38, v38
	v_cvt_pk_bf16_f32 v34, v34, v29
	ds_read_b32 v35, v93 offset:736
	global_store_dword v[100:101], v34, off offset:1216
	v_add_f32_e32 v38, 1.0, v38
	v_rcp_f32_e32 v38, v38
	v_exp_f32_e32 v31, v31
	s_waitcnt lgkmcnt(0)
	v_mul_f32_e32 v35, v36, v35
	v_mul_f32_e32 v22, 0xbfb8aa3b, v22
	v_mul_f32_e32 v38, 0xc1000000, v38
	v_mul_f32_e32 v38, v27, v38
	v_mul_f32_e32 v39, 0x3fb8aa3b, v38
	v_exp_f32_e32 v39, v39
	v_exp_f32_e32 v22, v22
	v_mul_f32_e32 v30, 0xc1000000, v30
	v_mul_f32_e32 v30, v27, v30
	v_sub_f32_e32 v40, 1.0, v39
	v_add_f32_e32 v39, 1.0, v39
	v_mul_f32_e32 v39, v40, v39
	v_sqrt_f32_e32 v39, v39
	v_add_f32_e32 v31, 1.0, v31
	v_rcp_f32_e32 v31, v31
	v_add_f32_e32 v22, 1.0, v22
	v_mul_f32_e32 v35, v35, v39
	v_add_f32_e32 v39, v102, v41
	v_mul_f32_e32 v39, 0xbfb8aa3b, v39
	v_exp_f32_e32 v39, v39
	v_cvt_pk_bf16_f32 v36, v38, v35
	ds_read_b32 v38, v93 offset:1008
	global_store_dword v[100:101], v36, off offset:2240
	v_add_f32_e32 v39, 1.0, v39
	v_rcp_f32_e32 v39, v39
	v_rcp_f32_e32 v22, v22
	s_waitcnt lgkmcnt(0)
	v_mul_f32_e32 v37, v37, v38
	v_mul_f32_e32 v31, 0xc1000000, v31
	v_mul_f32_e32 v39, 0xc1000000, v39
	v_mul_f32_e32 v39, v27, v39
	v_mul_f32_e32 v40, 0x3fb8aa3b, v39
	v_exp_f32_e32 v40, v40
	v_add_f32_e32 v23, v0, v23
	v_mul_f32_e32 v31, v27, v31
	v_mul_f32_e32 v23, 0xbfb8aa3b, v23
	v_sub_f32_e32 v41, 1.0, v40
	v_add_f32_e32 v40, 1.0, v40
	v_mul_f32_e32 v40, v41, v40
	v_sqrt_f32_e32 v40, v40
	v_exp_f32_e32 v23, v23
	v_add_f32_e32 v24, v0, v24
	v_mul_f32_e32 v24, 0xbfb8aa3b, v24
	v_mul_f32_e32 v37, v40, v37
	v_mul_f32_e32 v40, 0x3fb8aa3b, v30
	v_exp_f32_e32 v40, v40
	v_cvt_pk_bf16_f32 v38, v39, v37
	ds_read_b32 v39, v93 offset:4544
	global_store_dword v[100:101], v38, off offset:3264
	v_sub_f32_e32 v41, 1.0, v40
	v_add_f32_e32 v40, 1.0, v40
	v_mul_f32_e32 v40, v41, v40
	v_sqrt_f32_e32 v40, v40
	s_waitcnt lgkmcnt(0)
	v_mul_f32_e32 v22, v22, v39
	v_mul_f32_e32 v39, 0x3fb8aa3b, v31
	v_exp_f32_e32 v39, v39
	v_mul_f32_e32 v22, v40, v22
	v_cvt_pk_bf16_f32 v22, v30, v22
	ds_read_b32 v30, v93 offset:4816
	v_add_f32_e32 v23, 1.0, v23
	v_sub_f32_e32 v40, 1.0, v39
	v_add_f32_e32 v39, 1.0, v39
	v_rcp_f32_e32 v23, v23
	v_mul_f32_e32 v39, v40, v39
	v_sqrt_f32_e32 v39, v39
	global_store_dword v[74:75], v22, off offset:192
	s_waitcnt lgkmcnt(0)
	v_mul_f32_e32 v23, v23, v30
	v_exp_f32_e32 v24, v24
	v_mul_f32_e32 v23, v39, v23
	v_cvt_pk_bf16_f32 v23, v31, v23
	v_add_f32_e32 v31, v102, v32
	v_mul_f32_e32 v31, 0xbfb8aa3b, v31
	v_exp_f32_e32 v31, v31
	ds_read_b32 v30, v93 offset:5088
	v_add_f32_e32 v24, 1.0, v24
	v_rcp_f32_e32 v24, v24
	v_add_f32_e32 v31, 1.0, v31
	v_rcp_f32_e32 v31, v31
	global_store_dword v[74:75], v23, off offset:1216
	s_waitcnt lgkmcnt(0)
	v_mul_f32_e32 v24, v24, v30
	v_add_f32_e32 v0, v0, v25
	v_mul_f32_e32 v31, 0xc1000000, v31
	v_mul_f32_e32 v31, v27, v31
	v_mul_f32_e32 v32, 0x3fb8aa3b, v31
	v_exp_f32_e32 v32, v32
	v_mul_f32_e32 v0, 0xbfb8aa3b, v0
	v_exp_f32_e32 v0, v0
	v_lshlrev_b32_e32 v26, 16, v28
	v_sub_f32_e32 v39, 1.0, v32
	v_add_f32_e32 v32, 1.0, v32
	v_mul_f32_e32 v32, v39, v32
	v_sqrt_f32_e32 v32, v32
	v_add_f32_e32 v0, 1.0, v0
	v_lshlrev_b32_e32 v29, 16, v34
	v_lshlrev_b32_e32 v35, 16, v36
	v_mul_f32_e32 v24, v32, v24
	v_cvt_pk_bf16_f32 v24, v31, v24
	v_add_f32_e32 v31, v102, v33
	v_mul_f32_e32 v31, 0xbfb8aa3b, v31
	v_exp_f32_e32 v31, v31
	ds_read_b32 v30, v93 offset:5360
	v_rcp_f32_e32 v0, v0
	v_mul_f32_e32 v26, 0x3fb8aa3b, v26
	v_add_f32_e32 v31, 1.0, v31
	v_rcp_f32_e32 v31, v31
	v_mul_f32_e32 v29, 0x3fb8aa3b, v29
	v_mul_f32_e32 v35, 0x3fb8aa3b, v35
	v_exp_f32_e32 v26, v26
	v_mul_f32_e32 v25, 0xc1000000, v31
	v_mul_f32_e32 v25, v27, v25
	v_mul_f32_e32 v27, 0x3fb8aa3b, v25
	v_exp_f32_e32 v27, v27
	v_exp_f32_e32 v29, v29
	v_exp_f32_e32 v35, v35
	s_waitcnt lgkmcnt(0)
	v_mul_f32_e32 v0, v0, v30
	v_sub_f32_e32 v31, 1.0, v27
	v_add_f32_e32 v27, 1.0, v27
	v_mul_f32_e32 v27, v31, v27
	v_sqrt_f32_e32 v27, v27
	v_and_b32_e32 v28, 0xffff0000, v28
	v_and_b32_e32 v34, 0xffff0000, v34
	v_and_b32_e32 v36, 0xffff0000, v36
	v_and_b32_e32 v37, 0xffff0000, v38
	v_mul_f32_e32 v0, v27, v0
	s_and_b64 vcc, exec, s[38:39]
	global_store_dword v[74:75], v24, off offset:2240
	v_cvt_pk_bf16_f32 v0, v25, v0
	global_store_dword v[74:75], v0, off offset:3264
	s_cbranch_vccnz .LBB0_535
	v_fma_f32 v25, v35, v37, v36
	v_fma_f32 v25, v29, v25, v34
	v_fma_f32 v25, v26, v25, v28
	s_mov_b64 s[4:5], 0

; template <bool PASS2> ...
;     ...
;             float PA[8], PB[8];
; #pragma unroll
;             for (int e = 0; e < 8; ++e) { PA[e] = __shfl(Ap[e >> 2], (e & 3) * 16 + fr); PB[e] = __shfl(Bp[e >> 2], (e & 3) * 16 + fr); }
;             const size_t si = ((size_t)(b * NCH + c) * 2 + d) * 256 + chn;
;             if (!PASS2) {
;                 float At = 1.f, Bt = 0.f;
; #pragma unroll
;                 for (int e2 = 0; e2 < 8; ++e2) { const int e = d == 0 ? e2 : 7 - e2; Bt = PA[e] * Bt + PB[e]; At *= PA[e]; }
;                 if (fq == 0) { LRA[si] = At; LRB[si] = Bt; }
.LBB0_541:
	v_mul_f32_e32 v22, v28, v22
	v_mul_f32_e32 v0, v23, v0
	v_mul_f32_e32 v38, v22, v0
	v_mul_f32_e32 v0, v26, v29
	v_mul_f32_e32 v22, v35, v27
	v_mul_f32_e32 v24, v0, v22
	ds_bpermute_b32 v33, v76, v24
	ds_bpermute_b32 v0, v76, v25
	ds_bpermute_b32 v36, v59, v24
	ds_bpermute_b32 v22, v59, v25
	ds_bpermute_b32 v35, v58, v24
	ds_bpermute_b32 v23, v58, v25
	ds_bpermute_b32 v34, v77, v24
	ds_bpermute_b32 v24, v77, v25
	ds_bpermute_b32 v31, v76, v38
	ds_bpermute_b32 v28, v76, v37
	ds_bpermute_b32 v32, v59, v38
	ds_bpermute_b32 v27, v59, v37
	ds_bpermute_b32 v30, v58, v38
	ds_bpermute_b32 v26, v58, v37
	ds_bpermute_b32 v29, v77, v38
	ds_bpermute_b32 v25, v77, v37
	s_and_saveexec_b64 s[4:5], s[36:37]
	s_cbranch_execz .LBB0_501
	s_cmp_eq_u32 s64, 1
	s_cselect_b64 vcc, -1, 0
	s_cmp_eq_u32 s64, 2
	s_waitcnt lgkmcnt(0)
	v_cndmask_b32_e32 v37, v33, v36, vcc
	s_cselect_b64 vcc, -1, 0
	s_cmp_eq_u32 s64, 3
	v_cndmask_b32_e32 v37, v37, v35, vcc
	s_cselect_b64 vcc, -1, 0
	s_cmp_eq_u32 s64, 4
	v_cndmask_b32_e32 v37, v37, v34, vcc
	s_cselect_b64 vcc, -1, 0
	s_cmp_eq_u32 s64, 5
	v_cndmask_b32_e32 v37, v37, v31, vcc
	s_cselect_b64 vcc, -1, 0
	s_cmp_eq_u32 s64, 6
	v_cndmask_b32_e32 v37, v37, v32, vcc
	s_cselect_b64 vcc, -1, 0
	s_cmp_eq_u32 s64, 7
	v_cndmask_b32_e32 v37, v37, v30, vcc
	s_cselect_b64 vcc, -1, 0
	s_cmp_eq_u32 s62, 1
	v_cndmask_b32_e32 v37, v37, v29, vcc
	s_cselect_b64 vcc, -1, 0
	s_cmp_eq_u32 s62, 2
	v_cndmask_b32_e32 v40, v33, v36, vcc
	s_cselect_b64 vcc, -1, 0
	s_cmp_eq_u32 s62, 3
	v_cndmask_b32_e32 v40, v40, v35, vcc
	s_cselect_b64 vcc, -1, 0
	s_cmp_eq_u32 s62, 4
	v_cndmask_b32_e32 v40, v40, v34, vcc
	s_cselect_b64 vcc, -1, 0
	s_cmp_eq_u32 s62, 5
	v_cndmask_b32_e32 v40, v40, v31, vcc
	s_cselect_b64 vcc, -1, 0
	s_cmp_eq_u32 s62, 6
	v_cndmask_b32_e32 v40, v40, v32, vcc
	s_cselect_b64 vcc, -1, 0
	s_cmp_eq_u32 s62, 7
	v_cndmask_b32_e32 v40, v40, v30, vcc
	s_cselect_b64 vcc, -1, 0
	s_cmp_eq_u32 s60, 1
	v_cndmask_b32_e32 v40, v40, v29, vcc
	s_cselect_b64 vcc, -1, 0
	s_cmp_eq_u32 s60, 2
	v_cndmask_b32_e32 v42, v33, v36, vcc
	s_cselect_b64 vcc, -1, 0
	s_cmp_eq_u32 s60, 3
	v_cndmask_b32_e32 v42, v42, v35, vcc
	s_cselect_b64 vcc, -1, 0
	s_cmp_eq_u32 s60, 4
	v_cndmask_b32_e32 v42, v42, v34, vcc
	s_cselect_b64 vcc, -1, 0
	s_cmp_eq_u32 s60, 5
	v_cndmask_b32_e32 v42, v42, v31, vcc
	s_cselect_b64 vcc, -1, 0
	s_cmp_eq_u32 s60, 6
	v_cndmask_b32_e32 v42, v42, v32, vcc
	s_cselect_b64 vcc, -1, 0
	s_cmp_eq_u32 s60, 7
	v_cndmask_b32_e32 v42, v42, v30, vcc
	s_cselect_b64 vcc, -1, 0
	s_cmp_eq_u32 s58, 1
	v_cndmask_b32_e32 v42, v42, v29, vcc
	s_cselect_b64 vcc, -1, 0
	s_cmp_eq_u32 s58, 2
	v_cndmask_b32_e32 v43, v33, v36, vcc
	s_cselect_b64 vcc, -1, 0
	s_cmp_eq_u32 s58, 3
	v_cndmask_b32_e32 v43, v43, v35, vcc
	s_cselect_b64 vcc, -1, 0
	s_cmp_eq_u32 s58, 4
	v_cndmask_b32_e32 v43, v43, v34, vcc
	s_cselect_b64 vcc, -1, 0
	s_cmp_eq_u32 s58, 5
	v_cndmask_b32_e32 v43, v43, v31, vcc
	s_cselect_b64 vcc, -1, 0
	s_cmp_eq_u32 s58, 6
	v_cndmask_b32_e32 v43, v43, v32, vcc
	s_cselect_b64 vcc, -1, 0
	s_cmp_eq_u32 s58, 7
	v_cndmask_b32_e32 v43, v43, v30, vcc
	s_cselect_b64 vcc, -1, 0
	s_cmp_eq_u32 s56, 1
	v_cndmask_b32_e32 v43, v43, v29, vcc
	s_cselect_b64 vcc, -1, 0
	s_cmp_eq_u32 s56, 2
	v_cndmask_b32_e32 v44, v33, v36, vcc
	s_cselect_b64 vcc, -1, 0
	s_cmp_eq_u32 s56, 3
	v_cndmask_b32_e32 v44, v44, v35, vcc
	s_cselect_b64 vcc, -1, 0
	s_cmp_eq_u32 s56, 4
	v_cndmask_b32_e32 v44, v44, v34, vcc
	s_cselect_b64 vcc, -1, 0
	s_cmp_eq_u32 s56, 5
	v_cndmask_b32_e32 v44, v44, v31, vcc
	s_cselect_b64 vcc, -1, 0
	s_cmp_eq_u32 s56, 6
	v_cndmask_b32_e32 v44, v44, v32, vcc
	s_cselect_b64 vcc, -1, 0
	s_cmp_eq_u32 s56, 7
	v_cndmask_b32_e32 v44, v44, v30, vcc
	s_cselect_b64 vcc, -1, 0
	s_cmp_eq_u32 s54, 1
	v_cndmask_b32_e32 v44, v44, v29, vcc
	s_cselect_b64 vcc, -1, 0
	s_cmp_eq_u32 s54, 2
	v_cndmask_b32_e32 v45, v33, v36, vcc
	s_cselect_b64 vcc, -1, 0
	s_cmp_eq_u32 s54, 3
	v_cndmask_b32_e32 v45, v45, v35, vcc
	s_cselect_b64 vcc, -1, 0
	s_cmp_eq_u32 s54, 4
	v_cndmask_b32_e32 v45, v45, v34, vcc
	s_cselect_b64 vcc, -1, 0
	s_cmp_eq_u32 s54, 5
	v_cndmask_b32_e32 v45, v45, v31, vcc
	s_cselect_b64 vcc, -1, 0
	s_cmp_eq_u32 s54, 6
	v_cndmask_b32_e32 v45, v45, v32, vcc
	s_cselect_b64 vcc, -1, 0
	s_cmp_eq_u32 s54, 7
	v_cndmask_b32_e32 v45, v45, v30, vcc
	s_cselect_b64 vcc, -1, 0
	s_cmp_eq_u32 s52, 1
	v_cndmask_b32_e32 v45, v45, v29, vcc
	s_cselect_b64 vcc, -1, 0
	s_cmp_eq_u32 s52, 2
	v_cndmask_b32_e32 v46, v33, v36, vcc
	s_cselect_b64 vcc, -1, 0
	s_cmp_eq_u32 s52, 3
	v_cndmask_b32_e32 v46, v46, v35, vcc
	s_cselect_b64 vcc, -1, 0
	s_cmp_eq_u32 s52, 4
	v_cndmask_b32_e32 v46, v46, v34, vcc
	s_cselect_b64 vcc, -1, 0
	s_cmp_eq_u32 s52, 5
	v_cndmask_b32_e32 v46, v46, v31, vcc
	s_cselect_b64 vcc, -1, 0
	s_cmp_eq_u32 s52, 6
	v_cndmask_b32_e32 v46, v46, v32, vcc
	s_cselect_b64 vcc, -1, 0
	s_cmp_eq_u32 s52, 7
	v_cndmask_b32_e32 v46, v46, v30, vcc
	s_cselect_b64 vcc, -1, 0
	s_cmp_eq_u32 s50, 1
	v_cndmask_b32_e32 v46, v46, v29, vcc
	s_cselect_b64 vcc, -1, 0
	s_cmp_eq_u32 s50, 2
	v_cndmask_b32_e32 v33, v33, v36, vcc
	s_cselect_b64 vcc, -1, 0
	s_cmp_eq_u32 s50, 3
	v_cndmask_b32_e32 v33, v33, v35, vcc
	s_cselect_b64 vcc, -1, 0
	s_cmp_eq_u32 s50, 4
	v_cndmask_b32_e32 v33, v33, v34, vcc
	s_cselect_b64 vcc, -1, 0
	s_cmp_eq_u32 s50, 5
	v_cndmask_b32_e32 v31, v33, v31, vcc
	s_cselect_b64 vcc, -1, 0
	s_cmp_eq_u32 s50, 6
	v_cndmask_b32_e32 v31, v31, v32, vcc
	s_cselect_b64 vcc, -1, 0
	v_cndmask_b32_e32 v30, v31, v30, vcc
	v_cndmask_b32_e64 v31, v25, v0, s[48:49]
	v_fmac_f32_e32 v31, 0, v37
	v_cndmask_b32_e64 v32, v26, v22, s[48:49]
	v_fmac_f32_e32 v32, v40, v31
	v_cndmask_b32_e64 v31, v27, v23, s[48:49]
	v_mul_f32_e32 v41, v37, v40
	v_fmac_f32_e32 v31, v42, v32
	v_cndmask_b32_e64 v32, v28, v24, s[48:49]
	v_mul_f32_e32 v41, v42, v41
	v_fmac_f32_e32 v32, v43, v31
	v_cndmask_b32_e64 v24, v24, v28, s[48:49]
	v_mul_f32_e32 v41, v43, v41
	s_cmp_eq_u32 s50, 7
	v_fmac_f32_e32 v24, v44, v32
	v_cndmask_b32_e64 v23, v23, v27, s[48:49]
	v_mul_f32_e32 v41, v44, v41
	s_cselect_b64 vcc, -1, 0
	v_fmac_f32_e32 v23, v45, v24
	v_cndmask_b32_e64 v22, v22, v26, s[48:49]
	v_mov_b32_e32 v39, s67
	v_or_b32_e32 v38, s66, v96
	v_mul_f32_e32 v41, v45, v41
	v_cndmask_b32_e32 v29, v30, v29, vcc
	v_fmac_f32_e32 v22, v46, v23
	v_cndmask_b32_e64 v0, v0, v25, s[48:49]
	v_mul_f32_e32 v41, v46, v41
	v_fmac_f32_e32 v0, v29, v22
	v_lshlrev_b64 v[22:23], 2, v[38:39]
	v_mul_f32_e32 v30, v29, v41
	v_lshl_add_u64 v[24:25], s[44:45], 0, v[22:23]
	v_lshl_add_u64 v[22:23], s[42:43], 0, v[22:23]
	global_store_dword v[22:23], v30, off
	global_store_dword v[24:25], v0, off
	s_branch .LBB0_501

; #define LDX(tt) (((tt) >= 0 && (tt) < seqlen) ? bf1(xp[(size_t)(tt) * INP]) : 0.f)
; #define LDX(tt) (((tt) >= 0 && (tt) < seqlen) ? bf1(xp[(size_t)(tt) * INP]) : 0.f)
; template <bool PASS2> ...
;     const int fr = lane & 15, fq = lane >> 4;
;     const int blk = t & 3, c = (t >> 2) % NCH, b = (t >> 2) / NCH;
;     const int seqlen = c < 8 ? 256 : 2048, t0 = c < 8 ? c * 32 : (c - 8) * 32, rbase = c < 8 ? ML + b * 256 : b * 2048;
;     bf16x8 af[2][2];
;     if (!PASS2) {
;         const int ch = blk * 64 + lane;
;         const float w0 = convw[(l * 4 + 0) * 256 + ch], w1 = convw[(l * 4 + 1) * 256 + ch], w2 = convw[(l * 4 + 2) * 256 + ch], w3 = convw[(l * 4 + 3) * 256 + ch], cb = convb[l * 256 + ch];
;         const bf16_t* xp = P + (size_t)rbase * INP + OFF_LRU + ch;
;     ...
;         float xs[35];
; #pragma unroll
;         for (int s = 0; s < 35; ++s) xs[s] = LDX(t0 + s - 2);
.LBB0_548:
	s_ashr_i32 s4, s1, 2
	s_mov_b32 s25, s1
	s_mul_hi_i32 s1, s4, 0x38e38e39
	s_lshr_b32 s6, s1, 31
	s_ashr_i32 s1, s1, 4
	s_add_i32 s1, s1, s6
	s_mul_i32 s6, s1, 0x48
	s_sub_i32 s6, s4, s6
	s_lshl_b32 s7, s6, 5
	s_lshl_b32 s15, s1, 8
	s_add_i32 s14, s7, 0xffffff00
	s_addk_i32 s15, 0x4000
	s_lshl_b32 s1, s1, 11
	s_cmp_lt_i32 s6, 8
	s_movk_i32 s6, 0x800
	s_cselect_b32 s6, 0x100, s6
	s_cselect_b32 s38, s7, s14
	s_cselect_b32 s1, s15, s1
	s_lshl_b32 s5, s5, 6
	s_and_b32 s5, s5, 0xc0
	v_or_b32_e32 v9, s5, v95
	v_readlane_b32 s7, v254, 32
	v_readlane_b32 s48, v251, 24
	v_readlane_b32 s49, v251, 25
	s_waitcnt lgkmcnt(0)
	v_or_b32_e32 v0, s7, v9
	v_readlane_b32 s50, v251, 26
	v_readlane_b32 s51, v251, 27
	v_readlane_b32 s52, v251, 28
	v_readlane_b32 s53, v251, 29
	v_readlane_b32 s54, v251, 30
	v_readlane_b32 s55, v251, 31
	v_readlane_b32 s56, v251, 32
	v_readlane_b32 s57, v251, 33
	v_readlane_b32 s58, v251, 34
	v_readlane_b32 s59, v251, 35
	v_readlane_b32 s60, v251, 36
	v_readlane_b32 s61, v251, 37
	v_readlane_b32 s62, v251, 38
	v_readlane_b32 s63, v251, 39
	v_readlane_b32 s14, v254, 21
	s_mul_hi_i32 s7, s1, 0x2200
	v_lshl_add_u64 v[2:3], v[0:1], 2, s[62:63]
	v_readlane_b32 s48, v251, 40
	global_load_dword v7, v[2:3], off
	global_load_dword v6, v[2:3], off offset:1024
	global_load_dword v5, v[2:3], off offset:2048
	global_load_dword v4, v[2:3], off offset:3072
	v_or_b32_e32 v0, s14, v9
	v_readlane_b32 s49, v251, 41
	s_mul_i32 s14, s1, 0x2200
	s_add_u32 s18, s40, s14
	v_lshl_add_u64 v[2:3], v[0:1], 2, s[48:49]
	global_load_dword v8, v[2:3], off
	s_addc_u32 s19, s41, s7
	v_lshlrev_b32_e32 v0, 1, v9
	s_cmp_lt_i32 s38, 2
	v_lshl_add_u64 v[2:3], s[18:19], 0, v[0:1]
	s_cselect_b64 s[18:19], -1, 0
	s_cmp_le_i32 s38, s6
	s_cselect_b64 s[20:21], -1, 0
	s_cmp_gt_i32 s38, s6
	v_readlane_b32 s15, v254, 22
	s_cselect_b64 s[26:27], -1, 0
	s_mov_b64 s[14:15], 0x8eb8340
	s_or_b64 s[18:19], s[18:19], s[26:27]
	v_lshl_add_u64 v[2:3], v[2:3], 0, s[14:15]
	v_mov_b32_e32 v0, 0
	s_and_b64 vcc, exec, s[18:19]
	v_mov_b32_e32 v9, 0
	v_readlane_b32 s50, v251, 42
	v_readlane_b32 s51, v251, 43
	v_readlane_b32 s52, v251, 44
	v_readlane_b32 s53, v251, 45
	v_readlane_b32 s54, v251, 46
	v_readlane_b32 s55, v251, 47
	v_readlane_b32 s56, v251, 48
	v_readlane_b32 s57, v251, 49
	v_readlane_b32 s58, v251, 50
	v_readlane_b32 s59, v251, 51
	v_readlane_b32 s60, v251, 52
	v_readlane_b32 s61, v251, 53
	v_readlane_b32 s62, v251, 54
	v_readlane_b32 s63, v251, 55
	s_cbranch_vccnz .LBB0_550
	s_add_i32 s7, s38, -2
	v_mad_u64_u32 v[14:15], s[18:19], s7, v202, v[2:3]
	global_load_ushort v9, v[14:15], off
	s_nop 0
	s_nop 0
.LBB0_550:
	s_cmp_lt_i32 s38, 1
	s_cselect_b64 s[18:19], -1, 0
	s_xor_b64 s[20:21], s[20:21], -1
	s_or_b64 s[18:19], s[18:19], s[20:21]
	s_and_b64 vcc, exec, s[18:19]
	s_cbranch_vccnz .LBB0_552
	s_add_i32 s7, s38, -1
	v_mad_u64_u32 v[14:15], s[18:19], s7, v202, v[2:3]
	global_load_ushort v0, v[14:15], off
	s_nop 0
	s_nop 0
.LBB0_552:
	v_mov_b32_e32 v14, 0
	s_cmp_ge_u32 s38, s6
	v_mov_b32_e32 v15, 0
	s_cbranch_scc1 .LBB0_554
	v_mad_u64_u32 v[16:17], s[18:19], s38, v202, v[2:3]
	global_load_ushort v15, v[16:17], off
	s_nop 0
	s_nop 0
.LBB0_554:
	s_or_b32 s7, s38, 1
	s_cmp_gt_i32 s38, -1
	s_cselect_b64 s[20:21], -1, 0
	s_cmp_lt_i32 s7, s6
	s_cselect_b64 s[18:19], -1, 0
	s_and_b64 s[18:19], s[20:21], s[18:19]
	s_andn2_b64 vcc, exec, s[18:19]
	s_cbranch_vccnz .LBB0_556
	v_mad_u64_u32 v[16:17], s[18:19], s7, v202, v[2:3]
	global_load_ushort v14, v[16:17], off
	s_nop 0
	s_nop 0
.LBB0_556:
	s_or_b32 s7, s38, 2
	s_cmp_lt_i32 s7, s6
	s_cselect_b64 s[18:19], -1, 0
	s_and_b64 s[18:19], s[20:21], s[18:19]
	v_mov_b32_e32 v16, 0
	s_andn2_b64 vcc, exec, s[18:19]
	v_mov_b32_e32 v17, 0
	s_cbranch_vccnz .LBB0_558
	v_mad_u64_u32 v[18:19], s[18:19], s7, v202, v[2:3]
	global_load_ushort v17, v[18:19], off
	s_nop 0
	s_nop 0
.LBB0_558:
	s_or_b32 s7, s38, 3
	s_cmp_lt_i32 s7, s6
	s_cselect_b64 s[18:19], -1, 0
	s_and_b64 s[18:19], s[20:21], s[18:19]
	s_andn2_b64 vcc, exec, s[18:19]
	s_cbranch_vccnz .LBB0_560
	v_mad_u64_u32 v[18:19], s[18:19], s7, v202, v[2:3]
	global_load_ushort v16, v[18:19], off
	s_nop 0
	s_nop 0
.LBB0_560:
	s_or_b32 s7, s38, 4
	s_cmp_lt_i32 s7, s6
	s_cselect_b64 s[18:19], -1, 0
	s_and_b64 s[18:19], s[20:21], s[18:19]
	v_mov_b32_e32 v18, 0
	s_andn2_b64 vcc, exec, s[18:19]
	v_mov_b32_e32 v19, 0
	s_cbranch_vccnz .LBB0_562
	v_mad_u64_u32 v[20:21], s[18:19], s7, v202, v[2:3]
	global_load_ushort v19, v[20:21], off
	s_nop 0
	s_nop 0
.LBB0_562:
	s_or_b32 s7, s38, 5
	s_cmp_lt_i32 s7, s6
	s_cselect_b64 s[18:19], -1, 0
	s_and_b64 s[18:19], s[20:21], s[18:19]
	s_andn2_b64 vcc, exec, s[18:19]
	s_cbranch_vccnz .LBB0_564
	v_mad_u64_u32 v[20:21], s[18:19], s7, v202, v[2:3]
	global_load_ushort v18, v[20:21], off
	s_nop 0
	s_nop 0
.LBB0_564:
	s_or_b32 s7, s38, 6
	s_cmp_lt_i32 s7, s6
	s_cselect_b64 s[18:19], -1, 0
	s_and_b64 s[18:19], s[20:21], s[18:19]
	v_mov_b32_e32 v20, 0
	s_andn2_b64 vcc, exec, s[18:19]
	v_mov_b32_e32 v21, 0
	s_cbranch_vccnz .LBB0_566
	v_mad_u64_u32 v[22:23], s[18:19], s7, v202, v[2:3]
	global_load_ushort v21, v[22:23], off
	s_nop 0
	s_nop 0
.LBB0_566:
	s_or_b32 s7, s38, 7
	s_cmp_lt_i32 s7, s6
	s_cselect_b64 s[18:19], -1, 0
	s_and_b64 s[18:19], s[20:21], s[18:19]
	s_andn2_b64 vcc, exec, s[18:19]
	s_cbranch_vccnz .LBB0_568
	v_mad_u64_u32 v[22:23], s[18:19], s7, v202, v[2:3]
	global_load_ushort v20, v[22:23], off
	s_nop 0
	s_nop 0
.LBB0_568:
	s_or_b32 s7, s38, 8
	s_cmp_lt_i32 s7, s6
	s_cselect_b64 s[18:19], -1, 0
	s_and_b64 s[18:19], s[20:21], s[18:19]
	v_mov_b32_e32 v22, 0
	s_andn2_b64 vcc, exec, s[18:19]
	v_mov_b32_e32 v23, 0
	s_cbranch_vccnz .LBB0_570
	v_mad_u64_u32 v[24:25], s[18:19], s7, v202, v[2:3]
	global_load_ushort v23, v[24:25], off
	s_nop 0
	s_nop 0
; #define LDX(tt) (((tt) >= 0 && (tt) < seqlen) ? bf1(xp[(size_t)(tt) * INP]) : 0.f)
; #define LDX(tt) (((tt) >= 0 && (tt) < seqlen) ? bf1(xp[(size_t)(tt) * INP]) : 0.f)
; template <bool PASS2> ...
;     ...
;         float xs[35];
; #pragma unroll
;         for (int s = 0; s < 35; ++s) xs[s] = LDX(t0 + s - 2);
.LBB0_570:
	s_or_b32 s7, s38, 9
	s_cmp_lt_i32 s7, s6
	s_cselect_b64 s[18:19], -1, 0
	s_and_b64 s[18:19], s[20:21], s[18:19]
	s_andn2_b64 vcc, exec, s[18:19]
	s_cbranch_vccnz .LBB0_572
	v_mad_u64_u32 v[24:25], s[18:19], s7, v202, v[2:3]
	global_load_ushort v22, v[24:25], off
	s_nop 0
	s_nop 0
.LBB0_572:
	s_or_b32 s7, s38, 10
	s_cmp_lt_i32 s7, s6
	s_cselect_b64 s[18:19], -1, 0
	s_and_b64 s[18:19], s[20:21], s[18:19]
	v_mov_b32_e32 v24, 0
	s_andn2_b64 vcc, exec, s[18:19]
	v_mov_b32_e32 v25, 0
	s_cbranch_vccnz .LBB0_574
	v_mad_u64_u32 v[26:27], s[18:19], s7, v202, v[2:3]
	global_load_ushort v25, v[26:27], off
	s_nop 0
	s_nop 0
.LBB0_574:
	s_or_b32 s7, s38, 11
	s_cmp_lt_i32 s7, s6
	s_cselect_b64 s[18:19], -1, 0
	s_and_b64 s[18:19], s[20:21], s[18:19]
	s_andn2_b64 vcc, exec, s[18:19]
	s_cbranch_vccnz .LBB0_576
	v_mad_u64_u32 v[26:27], s[18:19], s7, v202, v[2:3]
	global_load_ushort v24, v[26:27], off
	s_nop 0
	s_nop 0
.LBB0_576:
	s_or_b32 s7, s38, 12
	s_cmp_lt_i32 s7, s6
	s_cselect_b64 s[18:19], -1, 0
	s_and_b64 s[18:19], s[20:21], s[18:19]
	v_mov_b32_e32 v26, 0
	s_andn2_b64 vcc, exec, s[18:19]
	v_mov_b32_e32 v27, 0
	s_cbranch_vccnz .LBB0_578
	v_mad_u64_u32 v[28:29], s[18:19], s7, v202, v[2:3]
	global_load_ushort v27, v[28:29], off
	s_nop 0
	s_nop 0
.LBB0_578:
	s_or_b32 s7, s38, 13
	s_cmp_lt_i32 s7, s6
	s_cselect_b64 s[18:19], -1, 0
	s_and_b64 s[18:19], s[20:21], s[18:19]
	s_andn2_b64 vcc, exec, s[18:19]
	s_cbranch_vccnz .LBB0_580
	v_mad_u64_u32 v[28:29], s[18:19], s7, v202, v[2:3]
	global_load_ushort v26, v[28:29], off
	s_nop 0
	s_nop 0
.LBB0_580:
	s_or_b32 s7, s38, 14
	s_cmp_lt_i32 s7, s6
	s_cselect_b64 s[18:19], -1, 0
	s_and_b64 s[18:19], s[20:21], s[18:19]
	v_mov_b32_e32 v28, 0
	s_andn2_b64 vcc, exec, s[18:19]
	v_mov_b32_e32 v29, 0
	s_cbranch_vccnz .LBB0_582
	v_mad_u64_u32 v[30:31], s[18:19], s7, v202, v[2:3]
	global_load_ushort v29, v[30:31], off
	s_nop 0
	s_nop 0
.LBB0_582:
	s_or_b32 s7, s38, 15
	s_cmp_lt_i32 s7, s6
	s_cselect_b64 s[18:19], -1, 0
	s_and_b64 s[18:19], s[20:21], s[18:19]
	s_andn2_b64 vcc, exec, s[18:19]
	s_cbranch_vccnz .LBB0_584
	v_mad_u64_u32 v[30:31], s[18:19], s7, v202, v[2:3]
	global_load_ushort v28, v[30:31], off
	s_nop 0
	s_nop 0
.LBB0_584:
	s_or_b32 s7, s38, 16
	s_cmp_lt_i32 s7, s6
	s_cselect_b64 s[18:19], -1, 0
	s_and_b64 s[18:19], s[20:21], s[18:19]
	v_mov_b32_e32 v30, 0
	s_andn2_b64 vcc, exec, s[18:19]
	v_mov_b32_e32 v31, 0
	s_cbranch_vccnz .LBB0_586
	v_mad_u64_u32 v[32:33], s[18:19], s7, v202, v[2:3]
	global_load_ushort v31, v[32:33], off
	s_nop 0
	s_nop 0
.LBB0_586:
	s_or_b32 s7, s38, 17
	s_cmp_lt_i32 s7, s6
	s_cselect_b64 s[18:19], -1, 0
	s_and_b64 s[18:19], s[20:21], s[18:19]
	s_andn2_b64 vcc, exec, s[18:19]
	s_cbranch_vccnz .LBB0_588
	v_mad_u64_u32 v[32:33], s[18:19], s7, v202, v[2:3]
	global_load_ushort v30, v[32:33], off
	s_nop 0
	s_nop 0
.LBB0_588:
	s_or_b32 s7, s38, 18
	s_cmp_lt_i32 s7, s6
	s_cselect_b64 s[18:19], -1, 0
	s_and_b64 s[18:19], s[20:21], s[18:19]
	v_mov_b32_e32 v32, 0
	s_andn2_b64 vcc, exec, s[18:19]
	v_mov_b32_e32 v33, 0
	s_cbranch_vccnz .LBB0_590
	v_mad_u64_u32 v[34:35], s[18:19], s7, v202, v[2:3]
	global_load_ushort v33, v[34:35], off
	s_nop 0
	s_nop 0
.LBB0_590:
	s_or_b32 s7, s38, 19
	s_cmp_lt_i32 s7, s6
	s_cselect_b64 s[18:19], -1, 0
	s_and_b64 s[18:19], s[20:21], s[18:19]
	s_andn2_b64 vcc, exec, s[18:19]
	s_cbranch_vccnz .LBB0_592
	v_mad_u64_u32 v[34:35], s[18:19], s7, v202, v[2:3]
	global_load_ushort v32, v[34:35], off
	s_nop 0
	s_nop 0
.LBB0_592:
	s_or_b32 s7, s38, 20
	s_cmp_lt_i32 s7, s6
	s_cselect_b64 s[18:19], -1, 0
	s_and_b64 s[18:19], s[20:21], s[18:19]
	v_mov_b32_e32 v34, 0
	s_andn2_b64 vcc, exec, s[18:19]
	v_mov_b32_e32 v35, 0
	s_cbranch_vccnz .LBB0_594
	v_mad_u64_u32 v[36:37], s[18:19], s7, v202, v[2:3]
	global_load_ushort v35, v[36:37], off
	s_nop 0
	s_nop 0
.LBB0_594:
	s_or_b32 s7, s38, 21
	s_cmp_lt_i32 s7, s6
	s_cselect_b64 s[18:19], -1, 0
	s_and_b64 s[18:19], s[20:21], s[18:19]
	s_andn2_b64 vcc, exec, s[18:19]
	s_cbranch_vccnz .LBB0_596
	v_mad_u64_u32 v[36:37], s[18:19], s7, v202, v[2:3]
	global_load_ushort v34, v[36:37], off
	s_nop 0
	s_nop 0
.LBB0_596:
	s_or_b32 s7, s38, 22
	s_cmp_lt_i32 s7, s6
	s_cselect_b64 s[18:19], -1, 0
	s_and_b64 s[18:19], s[20:21], s[18:19]
	v_mov_b32_e32 v36, 0
	s_andn2_b64 vcc, exec, s[18:19]
	v_mov_b32_e32 v37, 0
	s_cbranch_vccnz .LBB0_598
	v_mad_u64_u32 v[38:39], s[18:19], s7, v202, v[2:3]
	global_load_ushort v37, v[38:39], off
	s_nop 0
	s_nop 0
; #define LDX(tt) (((tt) >= 0 && (tt) < seqlen) ? bf1(xp[(size_t)(tt) * INP]) : 0.f)
; #define LDX(tt) (((tt) >= 0 && (tt) < seqlen) ? bf1(xp[(size_t)(tt) * INP]) : 0.f)
; template <bool PASS2> ...
;     ...
;         float xs[35];
; #pragma unroll
;         for (int s = 0; s < 35; ++s) xs[s] = LDX(t0 + s - 2);
; #pragma unroll
;         for (int s = 0; s < 32; ++s) xl[s * 68 + lane] = cb + w0 * xs[s] + w1 * xs[s + 1] + w2 * xs[s + 2] + w3 * xs[s + 3];
.LBB0_598:
	s_or_b32 s7, s38, 23
	s_cmp_lt_i32 s7, s6
	s_cselect_b64 s[18:19], -1, 0
	s_and_b64 s[18:19], s[20:21], s[18:19]
	s_andn2_b64 vcc, exec, s[18:19]
	s_cbranch_vccnz .LBB0_600
	v_mad_u64_u32 v[38:39], s[18:19], s7, v202, v[2:3]
	global_load_ushort v36, v[38:39], off
	s_nop 0
	s_nop 0
.LBB0_600:
	s_or_b32 s7, s38, 24
	s_cmp_lt_i32 s7, s6
	s_cselect_b64 s[18:19], -1, 0
	s_and_b64 s[18:19], s[20:21], s[18:19]
	v_mov_b32_e32 v38, 0
	s_andn2_b64 vcc, exec, s[18:19]
	v_mov_b32_e32 v39, 0
	s_cbranch_vccnz .LBB0_602
	v_mad_u64_u32 v[40:41], s[18:19], s7, v202, v[2:3]
	global_load_ushort v39, v[40:41], off
	s_nop 0
	s_nop 0
.LBB0_602:
	s_or_b32 s7, s38, 25
	s_cmp_lt_i32 s7, s6
	s_cselect_b64 s[18:19], -1, 0
	s_and_b64 s[18:19], s[20:21], s[18:19]
	s_andn2_b64 vcc, exec, s[18:19]
	s_cbranch_vccnz .LBB0_604
	v_mad_u64_u32 v[40:41], s[18:19], s7, v202, v[2:3]
	global_load_ushort v38, v[40:41], off
	s_nop 0
	s_nop 0
.LBB0_604:
	s_or_b32 s7, s38, 26
	s_cmp_lt_i32 s7, s6
	s_cselect_b64 s[18:19], -1, 0
	s_and_b64 s[18:19], s[20:21], s[18:19]
	v_mov_b32_e32 v40, 0
	s_andn2_b64 vcc, exec, s[18:19]
	v_mov_b32_e32 v41, 0
	s_cbranch_vccnz .LBB0_606
	v_mad_u64_u32 v[42:43], s[18:19], s7, v202, v[2:3]
	global_load_ushort v41, v[42:43], off
	s_nop 0
	s_nop 0
.LBB0_606:
	s_or_b32 s7, s38, 27
	s_cmp_lt_i32 s7, s6
	s_cselect_b64 s[18:19], -1, 0
	s_and_b64 s[18:19], s[20:21], s[18:19]
	s_andn2_b64 vcc, exec, s[18:19]
	s_cbranch_vccnz .LBB0_608
	v_mad_u64_u32 v[42:43], s[18:19], s7, v202, v[2:3]
	global_load_ushort v40, v[42:43], off
	s_nop 0
	s_nop 0
.LBB0_608:
	s_or_b32 s7, s38, 28
	s_cmp_lt_i32 s7, s6
	s_cselect_b64 s[18:19], -1, 0
	s_and_b64 s[18:19], s[20:21], s[18:19]
	v_mov_b32_e32 v42, 0
	s_andn2_b64 vcc, exec, s[18:19]
	v_mov_b32_e32 v43, 0
	s_cbranch_vccnz .LBB0_610
	v_mad_u64_u32 v[44:45], s[18:19], s7, v202, v[2:3]
	global_load_ushort v43, v[44:45], off
	s_nop 0
	s_nop 0
.LBB0_610:
	s_or_b32 s7, s38, 29
	s_cmp_lt_i32 s7, s6
	s_cselect_b64 s[18:19], -1, 0
	s_and_b64 s[18:19], s[20:21], s[18:19]
	s_andn2_b64 vcc, exec, s[18:19]
	s_cbranch_vccnz .LBB0_612
	v_mad_u64_u32 v[44:45], s[18:19], s7, v202, v[2:3]
	global_load_ushort v42, v[44:45], off
	s_nop 0
	s_nop 0
.LBB0_612:
	s_or_b32 s7, s38, 30
	s_cmpk_gt_i32 s38, 0xffe1
	s_cselect_b64 s[18:19], -1, 0
	s_cmp_lt_i32 s7, s6
	s_cselect_b64 s[20:21], -1, 0
	s_and_b64 s[18:19], s[18:19], s[20:21]
	v_mov_b32_e32 v44, 0
	s_andn2_b64 vcc, exec, s[18:19]
	v_mov_b32_e32 v45, 0
	s_cbranch_vccnz .LBB0_614
	v_mad_u64_u32 v[46:47], s[18:19], s7, v202, v[2:3]
	global_load_ushort v45, v[46:47], off
	s_nop 0
	s_nop 0
.LBB0_614:
	s_or_b32 s7, s38, 31
	s_cmpk_gt_i32 s38, 0xffe0
	s_cselect_b64 s[18:19], -1, 0
	s_cmp_lt_i32 s7, s6
	s_cselect_b64 s[20:21], -1, 0
	s_and_b64 s[18:19], s[18:19], s[20:21]
	s_andn2_b64 vcc, exec, s[18:19]
	s_cbranch_vccnz .LBB0_616
	v_mad_u64_u32 v[46:47], s[18:19], s7, v202, v[2:3]
	global_load_ushort v44, v[46:47], off
	s_nop 0
	s_nop 0
.LBB0_616:
	s_waitcnt vmcnt(0) lgkmcnt(0)
	v_lshlrev_b32_e32 v9, 16, v9
	v_lshlrev_b32_e32 v0, 16, v0
	v_lshlrev_b32_e32 v15, 16, v15
	v_lshlrev_b32_e32 v14, 16, v14
	v_lshlrev_b32_e32 v17, 16, v17
	v_lshlrev_b32_e32 v16, 16, v16
	v_lshlrev_b32_e32 v19, 16, v19
	v_lshlrev_b32_e32 v18, 16, v18
	v_lshlrev_b32_e32 v21, 16, v21
	v_lshlrev_b32_e32 v20, 16, v20
	v_lshlrev_b32_e32 v23, 16, v23
	v_lshlrev_b32_e32 v22, 16, v22
	v_lshlrev_b32_e32 v25, 16, v25
	v_lshlrev_b32_e32 v24, 16, v24
	v_lshlrev_b32_e32 v27, 16, v27
	v_lshlrev_b32_e32 v26, 16, v26
	v_lshlrev_b32_e32 v29, 16, v29
	v_lshlrev_b32_e32 v28, 16, v28
	v_lshlrev_b32_e32 v31, 16, v31
	v_lshlrev_b32_e32 v30, 16, v30
	v_lshlrev_b32_e32 v33, 16, v33
	v_lshlrev_b32_e32 v32, 16, v32
	v_lshlrev_b32_e32 v35, 16, v35
	v_lshlrev_b32_e32 v34, 16, v34
	v_lshlrev_b32_e32 v37, 16, v37
	v_lshlrev_b32_e32 v36, 16, v36
	v_lshlrev_b32_e32 v39, 16, v39
	v_lshlrev_b32_e32 v38, 16, v38
	v_lshlrev_b32_e32 v41, 16, v41
	v_lshlrev_b32_e32 v40, 16, v40
	v_lshlrev_b32_e32 v43, 16, v43
	v_lshlrev_b32_e32 v42, 16, v42
	v_lshlrev_b32_e32 v45, 16, v45
	v_lshlrev_b32_e32 v44, 16, v44
	s_nop 0
	s_nop 0
	s_nop 0
	s_nop 0
	s_nop 0
	s_nop 0
	s_nop 0
	s_nop 0
	s_nop 0
	s_nop 0
	s_nop 0
	s_nop 0
	s_nop 0
	s_add_i32 s7, s38, 32
	s_cmpk_gt_i32 s38, 0xffdf
	s_cselect_b64 s[18:19], -1, 0
	s_cmp_lt_i32 s7, s6
	s_cselect_b64 s[20:21], -1, 0
	s_and_b64 s[18:19], s[18:19], s[20:21]
	s_andn2_b64 vcc, exec, s[18:19]
	v_mov_b32_e32 v46, 0
	s_cbranch_vccnz .LBB0_618
	v_mad_u64_u32 v[2:3], s[6:7], s7, v202, v[2:3]
	global_load_ushort v2, v[2:3], off
	s_waitcnt vmcnt(0) lgkmcnt(0)
	v_lshlrev_b32_e32 v46, 16, v2

; template <bool PASS2> ...
;     ...
;         bf16x8 wfa[4][2], wfx[4][2]; float pba[4], pbx[4], plm[4], phin[4]; unsigned pkv[4][2][4];
;         unsigned* labd = LAB + ((size_t)d * MH + rbase + t0 + fq * 4) * 256 + blk * 64 + fr;
; #pragma unroll
;         for (int cb = 0; cb < 4; ++cb) {
;             const int chn = blk * 64 + cb * 16 + fr;
;             if (!PASS2) {
;                 const bf16_t* wa = WLRU + ((size_t)(((l * 2 + d) * 2 + 0) * 4 + blk) * 64 + cb * 16 + fr) * 64 + fq * 8;
; #pragma unroll
;                 for (int ks = 0; ks < 2; ++ks) { wfa[cb][ks] = asfrag(ld8(wa + ks * 32)); wfx[cb][ks] = asfrag(ld8(wa + 4 * 4096 + ks * 32)); }
;                 pba[cb] = b_a[(l * 2 + d) * 256 + chn]; pbx[cb] = b_x[(l * 2 + d) * 256 + chn]; plm[cb] = lam[(l * 2 + d) * 256 + chn];
;             } else {
;                 phin[cb] = LRH[((size_t)(b * NCH + c) * 2 + d) * 256 + chn];
; #pragma unroll
;                 for (int tb = 0; tb < 2; ++tb)
; #pragma unroll
;                     for (int q = 0; q < 4; ++q) pkv[cb][tb][q] = labd[(size_t)(tb * 16 + q) * 256 + cb * 16];
;             }
;         }
; #pragma unroll
;         for (int cb = 0; cb < 4; ++cb) {
;             const int chn = blk * 64 + cb * 16 + fr;
;             float av[2][4], bv[2][4], Ap[2], Bp[2];
;             if (!PASS2) {
;                 f32x4 ga[2], gx[2];
;                 ga[0] = ga[1] = gx[0] = gx[1] = (f32x4){0.f, 0.f, 0.f, 0.f};
; #pragma unroll
;                 for (int ks = 0; ks < 2; ++ks) {
; #pragma unroll
;                     for (int tb = 0; tb < 2; ++tb) { ga[tb] = MFMA16(af[tb][ks], wfa[cb][ks], ga[tb]); gx[tb] = MFMA16(af[tb][ks], wfx[cb][ks], gx[tb]); } }
;                 const float ba = pba[cb], bx = pbx[cb], sp = log1pf(__expf(-plm[cb]));
; #pragma unroll
;                 for (int tb = 0; tb < 2; ++tb)
; #pragma unroll
;                     for (int q = 0; q < 4; ++q) { const float xv = xl[(tb * 16 + fq * 4 + q) * 68 + cb * 16 + fr];
;                         const float r = sigm(ga[tb][q] + ba), ig = sigm(gx[tb][q] + bx), la = -8.f * r * sp;
;                         const float aa = __expf(la), om = (1.f - aa) * (1.f + aa), bb = __builtin_amdgcn_sqrtf(om) * (ig * xv);
;                         const unsigned pk = cvt_pk_bf16(la, bb);
;                         labd[(size_t)(tb * 16 + q) * 256 + cb * 16] = pk;
.LBB0_620:
	s_or_b32 s1, s4, s2
	s_waitcnt lgkmcnt(0)
	v_lshlrev_b32_e32 v0, 6, v94
	v_lshl_or_b32 v0, s1, 15, v0
	v_lshl_add_u64 v[26:27], v[0:1], 1, v[90:91]
	global_load_dwordx4 v[22:25], v[26:27], off
	global_load_dwordx4 v[66:69], v[26:27], off offset:64
	v_add_co_u32_e32 v124, vcc, s33, v26
	v_mov_b32_e32 v29, v1
	v_lshl_or_b32 v28, s1, 8, v94
	v_readlane_b32 s52, v251, 40
	v_addc_co_u32_e32 v125, vcc, 0, v27, vcc
	v_lshlrev_b64 v[28:29], 2, v[28:29]
	v_readlane_b32 s54, v251, 42
	v_readlane_b32 s55, v251, 43
	global_load_dwordx4 v[62:65], v[124:125], off
	v_readlane_b32 s58, v251, 46
	v_lshl_add_u64 v[126:127], s[54:55], 0, v[28:29]
	global_load_dword v115, v[126:127], off
	global_load_dwordx4 v[78:81], v[124:125], off offset:64
	v_readlane_b32 s59, v251, 47
	v_readlane_b32 s62, v251, 50
	v_readlane_b32 s63, v251, 51
	v_lshl_add_u64 v[74:75], s[58:59], 0, v[28:29]
	s_mov_b32 s1, 0x9000
	v_lshl_add_u64 v[76:77], s[62:63], 0, v[28:29]
	v_add_co_u32_e32 v28, vcc, s90, v26
	s_mul_i32 s88, s4, 0x4800
	s_nop 0
	v_addc_co_u32_e32 v29, vcc, 0, v27, vcc
	global_load_dwordx4 v[58:61], v[26:27], off offset:2048
	global_load_dwordx4 v[54:57], v[26:27], off offset:2112
	v_add_co_u32_e32 v26, vcc, s1, v26
	v_lshl_add_u64 v[30:31], v[102:103], 0, s[88:89]
	s_nop 0
	v_addc_co_u32_e32 v27, vcc, 0, v27, vcc
	v_lshlrev_b64 v[104:105], 10, v[30:31]
	global_load_dwordx4 v[46:49], v[28:29], off
	global_load_dwordx4 v[38:41], v[28:29], off offset:64
	global_load_dwordx4 v[50:53], v[26:27], off
	global_load_dwordx4 v[42:45], v[26:27], off offset:64
	v_lshl_add_u64 v[104:105], v[92:93], 0, v[104:105]
	s_xor_b64 s[50:51], s[48:49], -1
	s_mov_b64 s[20:21], -1
	v_readlane_b32 s53, v251, 41
	v_readlane_b32 s56, v251, 44
	v_readlane_b32 s57, v251, 45
	v_readlane_b32 s60, v251, 48
	v_readlane_b32 s61, v251, 49
	v_readlane_b32 s64, v251, 52
	v_readlane_b32 s65, v251, 53
	v_readlane_b32 s66, v251, 54
	v_readlane_b32 s67, v251, 55
	s_waitcnt vmcnt(0) lgkmcnt(0)
	v_mfma_f32_16x16x32_bf16 v[70:73], v[2:5], v[22:25], 0
	v_mfma_f32_16x16x32_bf16 v[82:85], v[14:17], v[22:25], 0
	global_load_dwordx4 v[30:33], v[28:29], off offset:2048
	global_load_dwordx4 v[22:25], v[28:29], off offset:2112
	global_load_dwordx4 v[34:37], v[26:27], off offset:2048
	s_nop 0
	global_load_dwordx4 v[26:29], v[26:27], off offset:2112
	s_nop 0
	global_load_dword v128, v[74:75], off
	global_load_dword v113, v[74:75], off offset:64
	global_load_dword v110, v[74:75], off offset:128
	global_load_dword v107, v[74:75], off offset:192
	global_load_dword v129, v[76:77], off
	global_load_dword v112, v[76:77], off offset:64
	global_load_dword v109, v[76:77], off offset:128
	global_load_dword v0, v[76:77], off offset:192
	v_mfma_f32_16x16x32_bf16 v[116:119], v[2:5], v[62:65], 0
	global_load_dword v114, v[126:127], off offset:64
	global_load_dword v111, v[126:127], off offset:128
	global_load_dword v108, v[126:127], off offset:192
	v_mfma_f32_16x16x32_bf16 v[120:123], v[14:17], v[62:65], 0
	v_mul_f32_e32 v62, 0xbfb8aa3b, v115
	v_exp_f32_e32 v115, v62
	v_mfma_f32_16x16x32_bf16 v[74:77], v[6:9], v[66:69], v[70:73]
	v_mfma_f32_16x16x32_bf16 v[70:73], v[18:21], v[66:69], v[82:85]
	global_load_dwordx4 v[66:69], v[124:125], off offset:2048
	global_load_dwordx4 v[62:65], v[124:125], off offset:2112
	s_waitcnt vmcnt(0)
	s_nop 3
	v_add_f32_e32 v74, v128, v74
	v_mfma_f32_16x16x32_bf16 v[82:85], v[6:9], v[78:81], v[116:119]
	v_mul_f32_e32 v74, 0xbfb8aa3b, v74
	v_exp_f32_e32 v74, v74
	v_add_f32_e32 v75, v128, v75
	v_add_f32_e32 v118, 1.0, v115
	v_add_f32_e32 v119, -1.0, v118
	v_frexp_mant_f32_e32 v124, v118
	v_cvt_f64_f32_e32 v[116:117], v118
	v_sub_f32_e32 v125, v119, v118
	v_frexp_exp_i32_f64_e32 v116, v[116:117]
	v_cmp_gt_f32_e32 vcc, s70, v124
	v_sub_f32_e32 v119, v115, v119
	v_add_f32_e32 v117, 1.0, v125
	v_subbrev_co_u32_e32 v116, vcc, 0, v116, vcc
	v_add_f32_e32 v117, v119, v117
	v_sub_u32_e32 v119, 0, v116
	v_ldexp_f32 v118, v118, v119
	v_ldexp_f32 v117, v117, v119
	v_add_f32_e32 v119, -1.0, v118
	v_add_f32_e32 v124, 1.0, v118
	v_add_f32_e32 v125, 1.0, v119
	v_add_f32_e32 v126, -1.0, v124
	v_sub_f32_e32 v125, v118, v125
	v_sub_f32_e32 v118, v118, v126
	v_add_f32_e32 v125, v117, v125
	v_add_f32_e32 v117, v117, v118
	v_add_f32_e32 v126, v124, v117
	v_rcp_f32_e32 v127, v126
	v_add_f32_e32 v118, v119, v125
	v_sub_f32_e32 v124, v126, v124
	v_sub_f32_e32 v119, v118, v119
	v_sub_f32_e32 v117, v117, v124
	v_mul_f32_e32 v124, v118, v127
	v_sub_f32_e32 v119, v125, v119
	v_mul_f32_e32 v125, v126, v124
	v_fma_f32 v130, v124, v126, -v125
	v_fmac_f32_e32 v130, v124, v117
	v_add_f32_e32 v131, v125, v130
	v_sub_f32_e32 v132, v118, v131
	v_sub_f32_e32 v118, v118, v132
	v_sub_f32_e32 v125, v131, v125
	v_sub_f32_e32 v118, v118, v131
	v_sub_f32_e32 v125, v125, v130
	v_add_f32_e32 v118, v119, v118
	v_add_f32_e32 v118, v125, v118
	v_add_f32_e32 v119, v132, v118
	v_mul_f32_e32 v125, v127, v119
	v_sub_f32_e32 v130, v132, v119
	v_mul_f32_e32 v131, v126, v125
	v_add_f32_e32 v118, v118, v130
	v_add_f32_e32 v130, v124, v125
	v_fma_f32 v126, v125, v126, -v131
	v_sub_f32_e32 v124, v130, v124
	v_fmac_f32_e32 v126, v125, v117
	v_sub_f32_e32 v117, v125, v124
	v_add_f32_e32 v124, v131, v126
	v_sub_f32_e32 v125, v124, v131
	v_sub_f32_e32 v131, v119, v124
	v_sub_f32_e32 v119, v119, v131
	v_sub_f32_e32 v119, v119, v124
	v_cvt_f32_i32_e32 v116, v116
	v_sub_f32_e32 v125, v125, v126
	v_add_f32_e32 v118, v118, v119
	v_add_f32_e32 v118, v125, v118
	v_add_f32_e32 v118, v131, v118
	v_mul_f32_e32 v118, v127, v118
	v_add_f32_e32 v117, v117, v118
	v_mul_f32_e32 v125, 0x3f317218, v116
	v_add_f32_e32 v118, v130, v117
	v_fma_f32 v126, v116, s71, -v125
; __device__ __forceinline__ unsigned cvt_pk_bf16(float lo, float hi) { unsigned r; asm volatile("v_cvt_pk_bf16_f32 %0, %1, %2" : "=v"(r) : "v"(lo), "v"(hi)); return r; }
; __device__ __forceinline__ float bflo(unsigned w) { return __uint_as_float(w << 16); }
; __device__ __forceinline__ float bfhi(unsigned w) { return __uint_as_float(w & 0xffff0000u); }
; __device__ __forceinline__ float sigm(float x) { return __builtin_amdgcn_rcpf(1.f + __expf(-x)); }
; template <bool PASS2> ...
;     ...
;                 const float ba = pba[cb], bx = pbx[cb], sp = log1pf(__expf(-plm[cb]));
; #pragma unroll
;                 for (int tb = 0; tb < 2; ++tb)
; #pragma unroll
;                     for (int q = 0; q < 4; ++q) { const float xv = xl[(tb * 16 + fq * 4 + q) * 68 + cb * 16 + fr];
;                         const float r = sigm(ga[tb][q] + ba), ig = sigm(gx[tb][q] + bx), la = -8.f * r * sp;
;                         const float aa = __expf(la), om = (1.f - aa) * (1.f + aa), bb = __builtin_amdgcn_sqrtf(om) * (ig * xv);
;                         const unsigned pk = cvt_pk_bf16(la, bb);
;                         labd[(size_t)(tb * 16 + q) * 256 + cb * 16] = pk;
;                         av[tb][q] = __expf(bflo(pk)); bv[tb][q] = bfhi(pk); }
	v_fmac_f32_e32 v126, 0xb102e308, v116
	v_sub_f32_e32 v116, v118, v130
	v_mul_f32_e32 v119, v118, v118
	v_sub_f32_e32 v116, v117, v116
	v_add_f32_e32 v117, v125, v126
	v_fmamk_f32 v124, v119, 0x3e9b6dac, v198
	v_sub_f32_e32 v125, v117, v125
	v_fmaak_f32 v124, v119, v124, 0x3f2aaada
	v_sub_f32_e32 v125, v126, v125
	v_ldexp_f32 v126, v118, 1
	v_mul_f32_e32 v118, v118, v119
	v_mul_f32_e32 v118, v118, v124
	v_add_f32_e32 v119, v126, v118
	v_sub_f32_e32 v124, v119, v126
	v_ldexp_f32 v116, v116, 1
	v_sub_f32_e32 v118, v118, v124
	v_add_f32_e32 v116, v116, v118
	v_add_f32_e32 v118, v119, v116
	v_sub_f32_e32 v119, v118, v119
	v_sub_f32_e32 v116, v116, v119
	v_add_f32_e32 v119, v117, v118
	v_sub_f32_e32 v124, v119, v117
	v_sub_f32_e32 v126, v119, v124
	v_sub_f32_e32 v117, v117, v126
	v_sub_f32_e32 v118, v118, v124
	v_add_f32_e32 v117, v118, v117
	v_add_f32_e32 v118, v125, v116
	v_sub_f32_e32 v124, v118, v125
	v_add_f32_e32 v117, v118, v117
	v_sub_f32_e32 v126, v118, v124
	v_add_f32_e32 v118, v119, v117
	v_sub_f32_e32 v125, v125, v126
	v_sub_f32_e32 v116, v116, v124
	v_sub_f32_e32 v119, v118, v119
	v_add_f32_e32 v116, v116, v125
	v_sub_f32_e32 v117, v117, v119
	v_add_f32_e32 v116, v116, v117
	v_add_f32_e32 v74, 1.0, v74
	v_add_f32_e32 v116, v118, v116
	v_cmp_neq_f32_e32 vcc, s12, v115
	v_rcp_f32_e32 v74, v74
	v_mul_f32_e32 v75, 0xbfb8aa3b, v75
	v_cndmask_b32_e32 v116, v203, v116, vcc
	v_cmp_ngt_f32_e32 vcc, -1.0, v115
	v_mul_f32_e32 v74, 0xc1000000, v74
	v_exp_f32_e32 v75, v75
	v_cndmask_b32_e32 v116, v204, v116, vcc
	v_cmp_neq_f32_e32 vcc, -1.0, v115
	v_add_f32_e32 v82, v129, v82
	v_add_f32_e32 v75, 1.0, v75
	v_cndmask_b32_e32 v116, v205, v116, vcc
	v_cmp_lt_f32_e64 vcc, |v115|, s13
	v_mul_f32_e32 v82, 0xbfb8aa3b, v82
	v_rcp_f32_e32 v75, v75
	v_cndmask_b32_e32 v115, v116, v115, vcc
	v_mul_f32_e32 v74, v74, v115
	v_mul_f32_e32 v116, 0x3fb8aa3b, v74
	v_exp_f32_e32 v116, v116
	v_exp_f32_e32 v82, v82
	v_mul_f32_e32 v75, 0xc1000000, v75
	ds_read_b32 v124, v106
	v_sub_f32_e32 v117, 1.0, v116
	v_add_f32_e32 v116, 1.0, v116
	v_mul_f32_e32 v116, v117, v116
	v_sqrt_f32_e32 v125, v116
	v_mfma_f32_16x16x32_bf16 v[116:119], v[18:21], v[78:81], v[120:123]
	v_add_f32_e32 v79, v129, v83
	v_add_f32_e32 v82, 1.0, v82
	v_mul_f32_e32 v79, 0xbfb8aa3b, v79
	v_mul_f32_e32 v75, v75, v115
	v_rcp_f32_e32 v82, v82
	v_exp_f32_e32 v79, v79
	v_mul_f32_e32 v80, 0x3fb8aa3b, v75
	v_exp_f32_e32 v80, v80
	s_waitcnt lgkmcnt(0)
	v_mul_f32_e32 v78, v124, v82
	v_add_f32_e32 v79, 1.0, v79
	v_mul_f32_e32 v78, v78, v125
	v_cvt_pk_bf16_f32 v74, v74, v78
	ds_read_b32 v81, v106 offset:272
	v_rcp_f32_e32 v82, v79
	v_sub_f32_e32 v79, 1.0, v80
	v_add_f32_e32 v80, 1.0, v80
	v_mul_f32_e32 v79, v79, v80
	v_sqrt_f32_e32 v80, v79
	global_store_dword v[104:105], v74, off
	v_lshlrev_b32_e32 v78, 16, v74
	v_and_b32_e32 v79, 0xffff0000, v74
	s_waitcnt lgkmcnt(0)
	v_mul_f32_e32 v74, v82, v81
	v_mul_f32_e32 v74, v74, v80
	v_cvt_pk_bf16_f32 v74, v75, v74
	v_add_f32_e32 v75, v128, v76
	v_mul_f32_e32 v75, 0xbfb8aa3b, v75
	v_exp_f32_e32 v75, v75
	v_add_f32_e32 v80, v129, v84
	v_mul_f32_e32 v80, 0xbfb8aa3b, v80
	v_exp_f32_e32 v80, v80
	v_add_f32_e32 v75, 1.0, v75
	v_rcp_f32_e32 v75, v75
	ds_read_b32 v82, v106 offset:544
	v_add_f32_e32 v80, 1.0, v80
	v_rcp_f32_e32 v83, v80
	v_mul_f32_e32 v75, 0xc1000000, v75
	v_mul_f32_e32 v75, v75, v115
	v_mul_f32_e32 v81, 0x3fb8aa3b, v75
	v_exp_f32_e32 v81, v81
	global_store_dword v[104:105], v74, off offset:1024
	v_lshlrev_b32_e32 v76, 16, v74
	v_add_f32_e32 v70, v128, v70
	v_sub_f32_e32 v80, 1.0, v81
	v_add_f32_e32 v81, 1.0, v81
	v_mul_f32_e32 v80, v80, v81
	v_sqrt_f32_e32 v81, v80
	v_and_b32_e32 v80, 0xffff0000, v74
	s_waitcnt lgkmcnt(0)
; __device__ __forceinline__ unsigned cvt_pk_bf16(float lo, float hi) { unsigned r; asm volatile("v_cvt_pk_bf16_f32 %0, %1, %2" : "=v"(r) : "v"(lo), "v"(hi)); return r; }
; __device__ __forceinline__ float bflo(unsigned w) { return __uint_as_float(w << 16); }
; __device__ __forceinline__ float bfhi(unsigned w) { return __uint_as_float(w & 0xffff0000u); }
; __device__ __forceinline__ float sigm(float x) { return __builtin_amdgcn_rcpf(1.f + __expf(-x)); }
; template <bool PASS2> ...
;     ...
;                 const float ba = pba[cb], bx = pbx[cb], sp = log1pf(__expf(-plm[cb]));
; #pragma unroll
;                 for (int tb = 0; tb < 2; ++tb)
; #pragma unroll
;                     for (int q = 0; q < 4; ++q) { const float xv = xl[(tb * 16 + fq * 4 + q) * 68 + cb * 16 + fr];
;                         const float r = sigm(ga[tb][q] + ba), ig = sigm(gx[tb][q] + bx), la = -8.f * r * sp;
;                         const float aa = __expf(la), om = (1.f - aa) * (1.f + aa), bb = __builtin_amdgcn_sqrtf(om) * (ig * xv);
;                         const unsigned pk = cvt_pk_bf16(la, bb);
;                         labd[(size_t)(tb * 16 + q) * 256 + cb * 16] = pk;
;                         av[tb][q] = __expf(bflo(pk)); bv[tb][q] = bfhi(pk); }
	v_mul_f32_e32 v74, v83, v82
	v_mul_f32_e32 v70, 0xbfb8aa3b, v70
	v_mul_f32_e32 v74, v74, v81
	v_cvt_pk_bf16_f32 v74, v75, v74
	v_add_f32_e32 v75, v128, v77
	v_mul_f32_e32 v75, 0xbfb8aa3b, v75
	v_exp_f32_e32 v75, v75
	v_add_f32_e32 v81, v129, v85
	v_mul_f32_e32 v81, 0xbfb8aa3b, v81
	v_exp_f32_e32 v81, v81
	v_add_f32_e32 v75, 1.0, v75
	v_rcp_f32_e32 v75, v75
	v_exp_f32_e32 v70, v70
	ds_read_b32 v83, v106 offset:816
	v_add_f32_e32 v81, 1.0, v81
	v_mul_f32_e32 v75, 0xc1000000, v75
	v_mul_f32_e32 v75, v75, v115
	v_mul_f32_e32 v82, 0x3fb8aa3b, v75
	v_exp_f32_e32 v82, v82
	v_rcp_f32_e32 v81, v81
	v_add_f32_e32 v70, 1.0, v70
	v_rcp_f32_e32 v70, v70
	v_sub_f32_e32 v84, 1.0, v82
	v_add_f32_e32 v82, 1.0, v82
	v_mul_f32_e32 v82, v84, v82
	v_sqrt_f32_e32 v82, v82
	s_waitcnt lgkmcnt(0)
	v_mul_f32_e32 v81, v81, v83
	global_store_dword v[104:105], v74, off offset:2048
	v_mul_f32_e32 v70, 0xc1000000, v70
	v_mul_f32_e32 v81, v81, v82
	v_cvt_pk_bf16_f32 v81, v75, v81
	v_add_f32_e32 v75, v129, v116
	v_mul_f32_e32 v75, 0xbfb8aa3b, v75
	v_add_f32_e32 v71, v128, v71
	v_exp_f32_e32 v75, v75
	v_mul_f32_e32 v70, v70, v115
	v_mul_f32_e32 v71, 0xbfb8aa3b, v71
	v_mul_f32_e32 v82, 0x3fb8aa3b, v70
	v_exp_f32_e32 v71, v71
	v_exp_f32_e32 v82, v82
	ds_read_b32 v83, v106 offset:4352
	v_add_f32_e32 v75, 1.0, v75
	v_rcp_f32_e32 v75, v75
	v_add_f32_e32 v71, 1.0, v71
	v_sub_f32_e32 v84, 1.0, v82
	v_add_f32_e32 v82, 1.0, v82
	v_rcp_f32_e32 v71, v71
	v_mul_f32_e32 v82, v84, v82
	v_sqrt_f32_e32 v84, v82
	v_lshlrev_b32_e32 v77, 16, v74
	v_and_b32_e32 v82, 0xffff0000, v74
	s_waitcnt lgkmcnt(0)
	v_mul_f32_e32 v74, v75, v83
	v_add_f32_e32 v83, v129, v117
	v_mul_f32_e32 v83, 0xbfb8aa3b, v83
	v_mul_f32_e32 v71, 0xc1000000, v71
	v_exp_f32_e32 v83, v83
	v_mul_f32_e32 v71, v71, v115
	v_mul_f32_e32 v74, v74, v84
	v_mul_f32_e32 v84, 0x3fb8aa3b, v71
	v_exp_f32_e32 v84, v84
	global_store_dword v[104:105], v81, off offset:3072
	v_cvt_pk_bf16_f32 v70, v70, v74
	ds_read_b32 v85, v106 offset:4624
	v_add_f32_e32 v83, 1.0, v83
	v_rcp_f32_e32 v83, v83
	v_sub_f32_e32 v116, 1.0, v84
	v_add_f32_e32 v84, 1.0, v84
	v_mul_f32_e32 v84, v116, v84
	v_add_f32_e32 v72, v128, v72
	v_sqrt_f32_e32 v84, v84
	v_mul_f32_e32 v72, 0xbfb8aa3b, v72
	s_waitcnt lgkmcnt(0)
	v_mul_f32_e32 v83, v83, v85
	v_exp_f32_e32 v85, v72
	v_add_co_u32_e32 v74, vcc, s0, v104
	v_mul_f32_e32 v72, v83, v84
	s_nop 0
	v_addc_co_u32_e32 v75, vcc, 0, v105, vcc
	global_store_dword v[74:75], v70, off
	v_cvt_pk_bf16_f32 v72, v71, v72
	v_add_f32_e32 v71, 1.0, v85
	v_rcp_f32_e32 v71, v71
	v_add_f32_e32 v83, v129, v118
	v_mul_f32_e32 v83, 0xbfb8aa3b, v83
	v_exp_f32_e32 v83, v83
	v_mul_f32_e32 v71, 0xc1000000, v71
	v_mul_f32_e32 v71, v71, v115
	v_mul_f32_e32 v84, 0x3fb8aa3b, v71
	v_exp_f32_e32 v84, v84
	ds_read_b32 v85, v106 offset:4896
	v_add_f32_e32 v83, 1.0, v83
	v_rcp_f32_e32 v83, v83
	v_sub_f32_e32 v116, 1.0, v84
	v_add_f32_e32 v84, 1.0, v84
	v_mul_f32_e32 v84, v116, v84
	v_add_f32_e32 v73, v128, v73
	v_sqrt_f32_e32 v84, v84
	v_mul_f32_e32 v73, 0xbfb8aa3b, v73
	v_exp_f32_e32 v73, v73
	s_waitcnt lgkmcnt(0)
	v_mul_f32_e32 v83, v83, v85
	v_mul_f32_e32 v83, v83, v84
	global_store_dword v[74:75], v72, off offset:1024
	v_cvt_pk_bf16_f32 v83, v71, v83
	v_add_f32_e32 v71, 1.0, v73
	v_rcp_f32_e32 v71, v71
	v_add_f32_e32 v73, v129, v119
	v_mul_f32_e32 v73, 0xbfb8aa3b, v73
	v_exp_f32_e32 v73, v73
	v_mul_f32_e32 v71, 0xc1000000, v71
	v_mul_f32_e32 v71, v71, v115
	v_mul_f32_e32 v84, 0x3fb8aa3b, v71
	v_exp_f32_e32 v84, v84
	ds_read_b32 v115, v106 offset:5168
	v_add_f32_e32 v73, 1.0, v73
	v_rcp_f32_e32 v73, v73
	v_sub_f32_e32 v85, 1.0, v84
	v_add_f32_e32 v84, 1.0, v84
	v_mul_f32_e32 v84, v85, v84
	v_mul_f32_e32 v78, 0x3fb8aa3b, v78
	v_mul_f32_e32 v76, 0x3fb8aa3b, v76
	v_mul_f32_e32 v77, 0x3fb8aa3b, v77
	v_sqrt_f32_e32 v84, v84
	v_exp_f32_e32 v78, v78
	v_exp_f32_e32 v76, v76
	v_exp_f32_e32 v77, v77
	s_waitcnt lgkmcnt(0)
	v_mul_f32_e32 v73, v73, v115
	v_and_b32_e32 v85, 0xffff0000, v81
	v_mul_f32_e32 v73, v73, v84
	s_and_b64 vcc, exec, s[50:51]
	global_store_dword v[74:75], v83, off offset:2048
	v_cvt_pk_bf16_f32 v84, v71, v73
	global_store_dword v[74:75], v84, off offset:3072
	s_cbranch_vccz .LBB0_622
	v_fma_f32 v71, v77, v85, v82
	v_fma_f32 v71, v76, v71, v80
	v_fma_f32 v73, v78, v71, v79
	s_mov_b64 s[20:21], 0

; template <bool PASS2> ...
;     ...
;             for (int tb = 0; tb < 2; ++tb) {
;                 Ap[tb] = (av[tb][0] * av[tb][1]) * (av[tb][2] * av[tb][3]);
;                 Bp[tb] = d == 0 ? ((bv[tb][0] * av[tb][1] + bv[tb][1]) * av[tb][2] + bv[tb][2]) * av[tb][3] + bv[tb][3]
;                                 : ((bv[tb][3] * av[tb][2] + bv[tb][2]) * av[tb][1] + bv[tb][1]) * av[tb][0] + bv[tb][0];
;             }
;             float PA[8], PB[8];
; #pragma unroll
;             for (int e = 0; e < 8; ++e) { PA[e] = __shfl(Ap[e >> 2], (e & 3) * 16 + fr); PB[e] = __shfl(Bp[e >> 2], (e & 3) * 16 + fr); }
;             const size_t si = ((size_t)(b * NCH + c) * 2 + d) * 256 + chn;
;             if (!PASS2) {
;                 float At = 1.f, Bt = 0.f;
; #pragma unroll
;                 for (int e2 = 0; e2 < 8; ++e2) { const int e = d == 0 ? e2 : 7 - e2; Bt = PA[e] * Bt + PB[e]; At *= PA[e]; }
.LBB0_629:
	v_mul_f32_e32 v70, v79, v70
	v_mul_f32_e32 v72, v72, v80
	v_mul_f32_e32 v82, v70, v72
	v_mul_f32_e32 v70, v78, v76
	v_mul_f32_e32 v71, v77, v71
	v_and_b32_e32 v77, 64, v199
	v_mul_f32_e32 v78, v70, v71
	v_or_b32_e32 v70, v77, v87
	v_or_b32_e32 v77, v77, v95
	v_lshlrev_b32_e32 v76, 2, v70
	v_lshl_or_b32 v77, v77, 2, v206
	ds_bpermute_b32 v83, v76, v78
	ds_bpermute_b32 v70, v76, v73
	ds_bpermute_b32 v117, v76, v78 offset:64
	ds_bpermute_b32 v71, v76, v73 offset:64
	ds_bpermute_b32 v85, v76, v78 offset:128
	ds_bpermute_b32 v72, v76, v73 offset:128
	ds_bpermute_b32 v118, v77, v78
	ds_bpermute_b32 v73, v77, v73
	ds_bpermute_b32 v115, v76, v82
	ds_bpermute_b32 v81, v76, v119
	ds_bpermute_b32 v116, v76, v82 offset:64
	ds_bpermute_b32 v80, v76, v119 offset:64
	ds_bpermute_b32 v84, v76, v82 offset:128
	ds_bpermute_b32 v79, v76, v119 offset:128
	ds_bpermute_b32 v82, v77, v82
	ds_bpermute_b32 v78, v77, v119
	s_mov_b32 s5, s89
	s_lshl_b64 s[4:5], s[4:5], 8
	s_or_b64 s[66:67], s[4:5], s[46:47]
	s_and_saveexec_b64 s[4:5], s[36:37]
	s_cbranch_execz .LBB0_631
	s_cmp_eq_u32 s64, 1
	s_cselect_b64 vcc, -1, 0
	s_cmp_eq_u32 s64, 2
	s_waitcnt lgkmcnt(0)
	v_cndmask_b32_e32 v119, v83, v117, vcc
	s_cselect_b64 vcc, -1, 0
	s_cmp_eq_u32 s64, 3
	v_cndmask_b32_e32 v119, v119, v85, vcc
	s_cselect_b64 vcc, -1, 0
	s_cmp_eq_u32 s64, 4
	v_cndmask_b32_e32 v119, v119, v118, vcc
	s_cselect_b64 vcc, -1, 0
	s_cmp_eq_u32 s64, 5
	v_cndmask_b32_e32 v119, v119, v115, vcc
	s_cselect_b64 vcc, -1, 0
	s_cmp_eq_u32 s64, 6
	v_cndmask_b32_e32 v119, v119, v116, vcc
	s_cselect_b64 vcc, -1, 0
	s_cmp_eq_u32 s64, 7
	v_cndmask_b32_e32 v119, v119, v84, vcc
	s_cselect_b64 vcc, -1, 0
	s_cmp_eq_u32 s62, 1
	v_cndmask_b32_e32 v119, v119, v82, vcc
	s_cselect_b64 vcc, -1, 0
	s_cmp_eq_u32 s62, 2
	v_cndmask_b32_e32 v122, v83, v117, vcc
	s_cselect_b64 vcc, -1, 0
	s_cmp_eq_u32 s62, 3
	v_cndmask_b32_e32 v122, v122, v85, vcc
	s_cselect_b64 vcc, -1, 0
	s_cmp_eq_u32 s62, 4
	v_cndmask_b32_e32 v122, v122, v118, vcc
	s_cselect_b64 vcc, -1, 0
	s_cmp_eq_u32 s62, 5
	v_cndmask_b32_e32 v122, v122, v115, vcc
	s_cselect_b64 vcc, -1, 0
	s_cmp_eq_u32 s62, 6
	v_cndmask_b32_e32 v122, v122, v116, vcc
	s_cselect_b64 vcc, -1, 0
	s_cmp_eq_u32 s62, 7
	v_cndmask_b32_e32 v122, v122, v84, vcc
	s_cselect_b64 vcc, -1, 0
	s_cmp_eq_u32 s60, 1
	v_cndmask_b32_e32 v122, v122, v82, vcc
	s_cselect_b64 vcc, -1, 0
	s_cmp_eq_u32 s60, 2
	v_cndmask_b32_e32 v124, v83, v117, vcc
	s_cselect_b64 vcc, -1, 0
	s_cmp_eq_u32 s60, 3
	v_cndmask_b32_e32 v124, v124, v85, vcc
	s_cselect_b64 vcc, -1, 0
	s_cmp_eq_u32 s60, 4
	v_cndmask_b32_e32 v124, v124, v118, vcc
	s_cselect_b64 vcc, -1, 0
	s_cmp_eq_u32 s60, 5
	v_cndmask_b32_e32 v124, v124, v115, vcc
	s_cselect_b64 vcc, -1, 0
	s_cmp_eq_u32 s60, 6
	v_cndmask_b32_e32 v124, v124, v116, vcc
	s_cselect_b64 vcc, -1, 0
	s_cmp_eq_u32 s60, 7
	v_cndmask_b32_e32 v124, v124, v84, vcc
	s_cselect_b64 vcc, -1, 0
	s_cmp_eq_u32 s58, 1
	v_cndmask_b32_e32 v124, v124, v82, vcc
	s_cselect_b64 vcc, -1, 0
	s_cmp_eq_u32 s58, 2
	v_cndmask_b32_e32 v125, v83, v117, vcc
	s_cselect_b64 vcc, -1, 0
	s_cmp_eq_u32 s58, 3
	v_cndmask_b32_e32 v125, v125, v85, vcc
	s_cselect_b64 vcc, -1, 0
	s_cmp_eq_u32 s58, 4
	v_cndmask_b32_e32 v125, v125, v118, vcc
	s_cselect_b64 vcc, -1, 0
	s_cmp_eq_u32 s58, 5
	v_cndmask_b32_e32 v125, v125, v115, vcc
	s_cselect_b64 vcc, -1, 0
	s_cmp_eq_u32 s58, 6
	v_cndmask_b32_e32 v125, v125, v116, vcc
	s_cselect_b64 vcc, -1, 0
	s_cmp_eq_u32 s58, 7
	v_cndmask_b32_e32 v125, v125, v84, vcc
	s_cselect_b64 vcc, -1, 0
	s_cmp_eq_u32 s56, 1
	v_cndmask_b32_e32 v125, v125, v82, vcc
	s_cselect_b64 vcc, -1, 0
	s_cmp_eq_u32 s56, 2
	v_cndmask_b32_e32 v126, v83, v117, vcc
	s_cselect_b64 vcc, -1, 0
	s_cmp_eq_u32 s56, 3
	v_cndmask_b32_e32 v126, v126, v85, vcc
	s_cselect_b64 vcc, -1, 0
	s_cmp_eq_u32 s56, 4
	v_cndmask_b32_e32 v126, v126, v118, vcc
	s_cselect_b64 vcc, -1, 0
	s_cmp_eq_u32 s56, 5
	v_cndmask_b32_e32 v126, v126, v115, vcc
	s_cselect_b64 vcc, -1, 0
	s_cmp_eq_u32 s56, 6
	v_cndmask_b32_e32 v126, v126, v116, vcc
	s_cselect_b64 vcc, -1, 0
	s_cmp_eq_u32 s56, 7
	v_cndmask_b32_e32 v126, v126, v84, vcc
	s_cselect_b64 vcc, -1, 0
	s_cmp_eq_u32 s54, 1
	v_cndmask_b32_e32 v126, v126, v82, vcc
	s_cselect_b64 vcc, -1, 0
	s_cmp_eq_u32 s54, 2
	v_cndmask_b32_e32 v127, v83, v117, vcc
	s_cselect_b64 vcc, -1, 0
	s_cmp_eq_u32 s54, 3
	v_cndmask_b32_e32 v127, v127, v85, vcc
	s_cselect_b64 vcc, -1, 0
	s_cmp_eq_u32 s54, 4
	v_cndmask_b32_e32 v127, v127, v118, vcc
	s_cselect_b64 vcc, -1, 0
	s_cmp_eq_u32 s54, 5
	v_cndmask_b32_e32 v127, v127, v115, vcc
	s_cselect_b64 vcc, -1, 0
	s_cmp_eq_u32 s54, 6
	v_cndmask_b32_e32 v127, v127, v116, vcc
	s_cselect_b64 vcc, -1, 0
	s_cmp_eq_u32 s54, 7
	v_cndmask_b32_e32 v127, v127, v84, vcc
	s_cselect_b64 vcc, -1, 0
	s_cmp_eq_u32 s52, 1
	v_cndmask_b32_e32 v127, v127, v82, vcc
	s_cselect_b64 vcc, -1, 0
	s_cmp_eq_u32 s52, 2
	v_cndmask_b32_e32 v128, v83, v117, vcc
	s_cselect_b64 vcc, -1, 0
	s_cmp_eq_u32 s52, 3
	v_cndmask_b32_e32 v128, v128, v85, vcc
	s_cselect_b64 vcc, -1, 0
	s_cmp_eq_u32 s52, 4
	v_cndmask_b32_e32 v128, v128, v118, vcc
	s_cselect_b64 vcc, -1, 0
	s_cmp_eq_u32 s52, 5
	v_cndmask_b32_e32 v128, v128, v115, vcc
	s_cselect_b64 vcc, -1, 0
	s_cmp_eq_u32 s52, 6
	v_cndmask_b32_e32 v128, v128, v116, vcc
	s_cselect_b64 vcc, -1, 0
	s_cmp_eq_u32 s52, 7
	v_cndmask_b32_e32 v128, v128, v84, vcc
	s_cselect_b64 vcc, -1, 0
	s_cmp_eq_u32 s50, 1
	v_cndmask_b32_e32 v128, v128, v82, vcc
	s_cselect_b64 vcc, -1, 0
	s_cmp_eq_u32 s50, 2
	v_cndmask_b32_e32 v83, v83, v117, vcc
	s_cselect_b64 vcc, -1, 0
	s_cmp_eq_u32 s50, 3
	v_cndmask_b32_e32 v83, v83, v85, vcc
	s_cselect_b64 vcc, -1, 0
	s_cmp_eq_u32 s50, 4
	v_cndmask_b32_e32 v83, v83, v118, vcc
; __device__ __forceinline__ float sigm(float x) { return __builtin_amdgcn_rcpf(1.f + __expf(-x)); }
; #define MFMA16(a, b, c) __builtin_amdgcn_mfma_f32_16x16x32_bf16((a), (b), (c), 0, 0, 0)
; template <bool PASS2> ...
;     ...
;                 for (int ks = 0; ks < 2; ++ks) {
; #pragma unroll
;                     for (int tb = 0; tb < 2; ++tb) { ga[tb] = MFMA16(af[tb][ks], wfa[cb][ks], ga[tb]); gx[tb] = MFMA16(af[tb][ks], wfx[cb][ks], gx[tb]); } }
;                 const float ba = pba[cb], bx = pbx[cb], sp = log1pf(__expf(-plm[cb]));
; #pragma unroll
;                 for (int tb = 0; tb < 2; ++tb)
; #pragma unroll
;                     for (int q = 0; q < 4; ++q) { const float xv = xl[(tb * 16 + fq * 4 + q) * 68 + cb * 16 + fr];
;                         const float r = sigm(ga[tb][q] + ba), ig = sigm(gx[tb][q] + bx), la = -8.f * r * sp;
;                         const float aa = __expf(la), om = (1.f - aa) * (1.f + aa), bb = __builtin_amdgcn_sqrtf(om) * (ig * xv);
;     ...
;                 float At = 1.f, Bt = 0.f;
; #pragma unroll
;                 for (int e2 = 0; e2 < 8; ++e2) { const int e = d == 0 ? e2 : 7 - e2; Bt = PA[e] * Bt + PB[e]; At *= PA[e]; }
;                 if (fq == 0) { LRA[si] = At; LRB[si] = Bt; }
	s_cselect_b64 vcc, -1, 0
	s_cmp_eq_u32 s50, 5
	v_cndmask_b32_e32 v83, v83, v115, vcc
	s_cselect_b64 vcc, -1, 0
	s_cmp_eq_u32 s50, 6
	v_cndmask_b32_e32 v83, v83, v116, vcc
	s_cselect_b64 vcc, -1, 0
	v_cndmask_b32_e32 v83, v83, v84, vcc
	v_cndmask_b32_e64 v84, v78, v70, s[48:49]
	v_fmac_f32_e32 v84, 0, v119
	v_cndmask_b32_e64 v85, v79, v71, s[48:49]
	v_fmac_f32_e32 v85, v122, v84
	v_cndmask_b32_e64 v84, v80, v72, s[48:49]
	v_mul_f32_e32 v123, v119, v122
	v_fmac_f32_e32 v84, v124, v85
	v_cndmask_b32_e64 v85, v81, v73, s[48:49]
	v_mul_f32_e32 v123, v124, v123
	v_fmac_f32_e32 v85, v125, v84
	v_cndmask_b32_e64 v73, v73, v81, s[48:49]
	v_mul_f32_e32 v123, v125, v123
	s_cmp_eq_u32 s50, 7
	v_fmac_f32_e32 v73, v126, v85
	v_cndmask_b32_e64 v72, v72, v80, s[48:49]
	v_mul_f32_e32 v123, v126, v123
	s_cselect_b64 vcc, -1, 0
	v_fmac_f32_e32 v72, v127, v73
	v_cndmask_b32_e64 v71, v71, v79, s[48:49]
	v_mov_b32_e32 v121, s67
	v_or_b32_e32 v120, s66, v94
	v_mul_f32_e32 v123, v127, v123
	v_cndmask_b32_e32 v82, v83, v82, vcc
	v_fmac_f32_e32 v71, v128, v72
	v_cndmask_b32_e64 v78, v70, v78, s[48:49]
	v_mul_f32_e32 v123, v128, v123
	v_fmac_f32_e32 v78, v82, v71
	v_lshlrev_b64 v[70:71], 2, v[120:121]
	v_mul_f32_e32 v83, v82, v123
	v_lshl_add_u64 v[72:73], s[44:45], 0, v[70:71]
	v_lshl_add_u64 v[70:71], s[42:43], 0, v[70:71]
	global_store_dword v[70:71], v83, off
	global_store_dword v[72:73], v78, off
.LBB0_631:
	s_or_b64 exec, exec, s[4:5]
	s_waitcnt lgkmcnt(0)
	v_mfma_f32_16x16x32_bf16 v[70:73], v[2:5], v[58:61], 0
	s_mov_b64 s[4:5], -1
	v_mfma_f32_16x16x32_bf16 v[78:81], v[2:5], v[66:69], 0
	v_mfma_f32_16x16x32_bf16 v[58:61], v[14:17], v[58:61], 0
	v_mfma_f32_16x16x32_bf16 v[82:85], v[14:17], v[66:69], 0
	v_mfma_f32_16x16x32_bf16 v[70:73], v[6:9], v[54:57], v[70:73]
	v_mfma_f32_16x16x32_bf16 v[66:69], v[6:9], v[62:65], v[78:81]
	v_mfma_f32_16x16x32_bf16 v[58:61], v[18:21], v[54:57], v[58:61]
	v_mfma_f32_16x16x32_bf16 v[54:57], v[18:21], v[62:65], v[82:85]
	v_mul_f32_e32 v62, 0xbfb8aa3b, v114
	v_exp_f32_e32 v64, v62
	s_nop 3
	v_add_f32_e32 v67, v112, v67
	v_mul_f32_e32 v67, 0xbfb8aa3b, v67
	v_exp_f32_e32 v67, v67
	v_add_f32_e32 v65, 1.0, v64
	v_add_f32_e32 v62, -1.0, v65
	v_sub_f32_e32 v63, v62, v65
	v_add_f32_e32 v63, 1.0, v63
	v_sub_f32_e32 v62, v64, v62
	v_add_f32_e32 v78, v62, v63
	v_frexp_mant_f32_e32 v62, v65
	v_cmp_gt_f32_e32 vcc, s70, v62
	v_cvt_f64_f32_e32 v[62:63], v65
	v_frexp_exp_i32_f64_e32 v62, v[62:63]
	v_subbrev_co_u32_e32 v62, vcc, 0, v62, vcc
	v_sub_u32_e32 v63, 0, v62
	v_ldexp_f32 v65, v65, v63
	v_ldexp_f32 v63, v78, v63
	v_add_f32_e32 v78, -1.0, v65
	v_add_f32_e32 v79, 1.0, v78
	v_sub_f32_e32 v79, v65, v79
	v_add_f32_e32 v79, v63, v79
	v_add_f32_e32 v80, v78, v79
	v_sub_f32_e32 v78, v80, v78
	v_sub_f32_e32 v78, v79, v78
	v_add_f32_e32 v79, 1.0, v65
	v_add_f32_e32 v81, -1.0, v79
	v_sub_f32_e32 v65, v65, v81
	v_add_f32_e32 v63, v63, v65
	v_add_f32_e32 v65, v79, v63
	v_sub_f32_e32 v79, v65, v79
	v_sub_f32_e32 v63, v63, v79
	v_rcp_f32_e32 v79, v65
	v_cvt_f32_i32_e32 v62, v62
	v_cmp_neq_f32_e32 vcc, s12, v64
	v_add_f32_e32 v67, 1.0, v67
	v_mul_f32_e32 v81, v80, v79
	v_mul_f32_e32 v82, v65, v81
	v_fma_f32 v83, v81, v65, -v82
	v_fmac_f32_e32 v83, v81, v63
	v_add_f32_e32 v84, v82, v83
	v_sub_f32_e32 v85, v80, v84
	v_sub_f32_e32 v80, v80, v85
	v_sub_f32_e32 v82, v84, v82
	v_sub_f32_e32 v80, v80, v84
	v_add_f32_e32 v78, v78, v80
	v_sub_f32_e32 v80, v82, v83
	v_add_f32_e32 v78, v80, v78
	v_add_f32_e32 v80, v85, v78
	v_mul_f32_e32 v82, v79, v80
	v_mul_f32_e32 v83, v65, v82
	v_fma_f32 v65, v82, v65, -v83
	v_fmac_f32_e32 v65, v82, v63
	v_sub_f32_e32 v63, v85, v80
	v_add_f32_e32 v63, v78, v63
	v_add_f32_e32 v78, v83, v65
	v_sub_f32_e32 v84, v80, v78
	v_sub_f32_e32 v80, v80, v84
	v_sub_f32_e32 v83, v78, v83
	v_sub_f32_e32 v78, v80, v78
	v_add_f32_e32 v63, v63, v78
	v_sub_f32_e32 v65, v83, v65
	v_add_f32_e32 v63, v65, v63
	v_add_f32_e32 v65, v81, v82
	v_add_f32_e32 v63, v84, v63
	v_sub_f32_e32 v78, v65, v81
	v_mul_f32_e32 v63, v79, v63
	v_sub_f32_e32 v78, v82, v78
	v_add_f32_e32 v63, v78, v63
	v_mul_f32_e32 v81, 0x3f317218, v62
	v_add_f32_e32 v78, v65, v63
	v_fma_f32 v82, v62, s71, -v81
	v_mul_f32_e32 v79, v78, v78
	v_fmac_f32_e32 v82, 0xb102e308, v62
	v_sub_f32_e32 v62, v78, v65
	v_fmamk_f32 v80, v79, 0x3e9b6dac, v198
	v_sub_f32_e32 v62, v63, v62
	v_add_f32_e32 v63, v81, v82
	v_fmaak_f32 v80, v79, v80, 0x3f2aaada
	v_sub_f32_e32 v65, v63, v81
	v_ldexp_f32 v81, v78, 1
	v_mul_f32_e32 v78, v78, v79
	v_mul_f32_e32 v78, v78, v80
	v_add_f32_e32 v79, v81, v78
	v_sub_f32_e32 v80, v79, v81
	v_ldexp_f32 v62, v62, 1
	v_sub_f32_e32 v78, v78, v80
	v_add_f32_e32 v62, v62, v78
	v_add_f32_e32 v78, v79, v62
	v_sub_f32_e32 v79, v78, v79
	v_sub_f32_e32 v62, v62, v79
	v_add_f32_e32 v79, v63, v78
	v_sub_f32_e32 v80, v79, v63
	v_sub_f32_e32 v81, v79, v80
	v_sub_f32_e32 v65, v82, v65
	v_sub_f32_e32 v63, v63, v81
	v_sub_f32_e32 v78, v78, v80
	v_add_f32_e32 v63, v78, v63
	v_add_f32_e32 v78, v65, v62
	v_sub_f32_e32 v80, v78, v65
	v_sub_f32_e32 v81, v78, v80
	v_sub_f32_e32 v65, v65, v81
	v_sub_f32_e32 v62, v62, v80
	v_add_f32_e32 v63, v78, v63
	v_add_f32_e32 v62, v62, v65
	v_add_f32_e32 v65, v79, v63
	v_sub_f32_e32 v78, v65, v79
	v_sub_f32_e32 v63, v63, v78
	v_add_f32_e32 v62, v62, v63
	v_add_f32_e32 v62, v65, v62
	v_cndmask_b32_e32 v62, v203, v62, vcc
	v_cmp_ngt_f32_e32 vcc, -1.0, v64
	v_add_f32_e32 v65, v112, v66
	v_mul_f32_e32 v65, 0xbfb8aa3b, v65
	v_cndmask_b32_e32 v62, v204, v62, vcc
	v_cmp_neq_f32_e32 vcc, -1.0, v64
	v_exp_f32_e32 v65, v65
	v_rcp_f32_e32 v67, v67
	v_cndmask_b32_e32 v62, v205, v62, vcc
	v_cmp_lt_f32_e64 vcc, |v64|, s13
	v_add_f32_e32 v65, 1.0, v65
	v_rcp_f32_e32 v65, v65
	v_cndmask_b32_e32 v63, v62, v64, vcc
	v_add_f32_e32 v64, v113, v70
	v_mul_f32_e32 v64, 0xbfb8aa3b, v64
	v_exp_f32_e32 v64, v64
	ds_read_b32 v62, v106 offset:64
	v_add_f32_e32 v68, v112, v68
	v_mul_f32_e32 v68, 0xbfb8aa3b, v68
	v_add_f32_e32 v64, 1.0, v64
	v_rcp_f32_e32 v64, v64
	s_waitcnt lgkmcnt(0)
; __device__ __forceinline__ unsigned cvt_pk_bf16(float lo, float hi) { unsigned r; asm volatile("v_cvt_pk_bf16_f32 %0, %1, %2" : "=v"(r) : "v"(lo), "v"(hi)); return r; }
; __device__ __forceinline__ float bflo(unsigned w) { return __uint_as_float(w << 16); }
; __device__ __forceinline__ float bfhi(unsigned w) { return __uint_as_float(w & 0xffff0000u); }
; __device__ __forceinline__ float sigm(float x) { return __builtin_amdgcn_rcpf(1.f + __expf(-x)); }
; template <bool PASS2> ...
;     ...
;                     for (int q = 0; q < 4; ++q) { const float xv = xl[(tb * 16 + fq * 4 + q) * 68 + cb * 16 + fr];
;                         const float r = sigm(ga[tb][q] + ba), ig = sigm(gx[tb][q] + bx), la = -8.f * r * sp;
;                         const float aa = __expf(la), om = (1.f - aa) * (1.f + aa), bb = __builtin_amdgcn_sqrtf(om) * (ig * xv);
;                         const unsigned pk = cvt_pk_bf16(la, bb);
;                         labd[(size_t)(tb * 16 + q) * 256 + cb * 16] = pk;
;                         av[tb][q] = __expf(bflo(pk)); bv[tb][q] = bfhi(pk); }
	v_mul_f32_e32 v62, v62, v65
	v_exp_f32_e32 v68, v68
	v_add_f32_e32 v58, v113, v58
	v_mul_f32_e32 v64, 0xc1000000, v64
	v_mul_f32_e32 v64, v63, v64
	v_mul_f32_e32 v66, 0x3fb8aa3b, v64
	v_exp_f32_e32 v66, v66
	v_add_f32_e32 v68, 1.0, v68
	v_rcp_f32_e32 v68, v68
	v_add_f32_e32 v69, v112, v69
	v_sub_f32_e32 v70, 1.0, v66
	v_add_f32_e32 v66, 1.0, v66
	v_mul_f32_e32 v66, v70, v66
	v_sqrt_f32_e32 v66, v66
	v_mul_f32_e32 v58, 0xbfb8aa3b, v58
	v_mul_f32_e32 v69, 0xbfb8aa3b, v69
	v_exp_f32_e32 v58, v58
	v_mul_f32_e32 v62, v62, v66
	v_add_f32_e32 v66, v113, v71
	v_mul_f32_e32 v66, 0xbfb8aa3b, v66
	v_exp_f32_e32 v66, v66
	v_cvt_pk_bf16_f32 v64, v64, v62
	ds_read_b32 v65, v106 offset:336
	global_store_dword v[104:105], v64, off offset:64
	v_add_f32_e32 v66, 1.0, v66
	v_rcp_f32_e32 v66, v66
	v_exp_f32_e32 v69, v69
	s_waitcnt lgkmcnt(0)
	v_mul_f32_e32 v65, v67, v65
	v_add_f32_e32 v58, 1.0, v58
	v_mul_f32_e32 v66, 0xc1000000, v66
	v_mul_f32_e32 v66, v63, v66
	v_mul_f32_e32 v70, 0x3fb8aa3b, v66
	v_exp_f32_e32 v70, v70
	v_add_f32_e32 v69, 1.0, v69
	v_rcp_f32_e32 v58, v58
	v_add_f32_e32 v59, v113, v59
	v_sub_f32_e32 v71, 1.0, v70
	v_add_f32_e32 v70, 1.0, v70
	v_mul_f32_e32 v70, v71, v70
	v_sqrt_f32_e32 v70, v70
	v_rcp_f32_e32 v69, v69
	v_mul_f32_e32 v59, 0xbfb8aa3b, v59
	v_add_f32_e32 v54, v112, v54
	v_mul_f32_e32 v65, v65, v70
	v_add_f32_e32 v70, v113, v72
	v_mul_f32_e32 v70, 0xbfb8aa3b, v70
	v_exp_f32_e32 v70, v70
	v_cvt_pk_bf16_f32 v66, v66, v65
	ds_read_b32 v67, v106 offset:608
	global_store_dword v[104:105], v66, off offset:1088
	v_add_f32_e32 v70, 1.0, v70
	v_rcp_f32_e32 v70, v70
	v_exp_f32_e32 v59, v59
	s_waitcnt lgkmcnt(0)
	v_mul_f32_e32 v67, v68, v67
	v_mul_f32_e32 v54, 0xbfb8aa3b, v54
	v_mul_f32_e32 v70, 0xc1000000, v70
	v_mul_f32_e32 v70, v63, v70
	v_mul_f32_e32 v71, 0x3fb8aa3b, v70
	v_exp_f32_e32 v71, v71
	v_exp_f32_e32 v54, v54
	v_mul_f32_e32 v58, 0xc1000000, v58
	v_mul_f32_e32 v58, v63, v58
	v_sub_f32_e32 v72, 1.0, v71
	v_add_f32_e32 v71, 1.0, v71
	v_mul_f32_e32 v71, v72, v71
	v_sqrt_f32_e32 v71, v71
	v_add_f32_e32 v59, 1.0, v59
	v_rcp_f32_e32 v59, v59
	v_add_f32_e32 v54, 1.0, v54
	v_mul_f32_e32 v67, v67, v71
	v_add_f32_e32 v71, v113, v73
	v_mul_f32_e32 v71, 0xbfb8aa3b, v71
	v_exp_f32_e32 v71, v71
	v_cvt_pk_bf16_f32 v68, v70, v67
	ds_read_b32 v70, v106 offset:880
	global_store_dword v[104:105], v68, off offset:2112
	v_add_f32_e32 v71, 1.0, v71
	v_rcp_f32_e32 v71, v71
	v_rcp_f32_e32 v54, v54
	s_waitcnt lgkmcnt(0)
	v_mul_f32_e32 v69, v69, v70
	v_mul_f32_e32 v59, 0xc1000000, v59
	v_mul_f32_e32 v71, 0xc1000000, v71
	v_mul_f32_e32 v71, v63, v71
	v_mul_f32_e32 v72, 0x3fb8aa3b, v71
	v_exp_f32_e32 v72, v72
	v_add_f32_e32 v55, v112, v55
	v_mul_f32_e32 v59, v63, v59
	v_mul_f32_e32 v55, 0xbfb8aa3b, v55
	v_sub_f32_e32 v73, 1.0, v72
	v_add_f32_e32 v72, 1.0, v72
	v_mul_f32_e32 v72, v73, v72
	v_sqrt_f32_e32 v72, v72
	v_exp_f32_e32 v55, v55
	v_add_f32_e32 v56, v112, v56
	v_mul_f32_e32 v56, 0xbfb8aa3b, v56
	v_mul_f32_e32 v69, v72, v69
	v_mul_f32_e32 v72, 0x3fb8aa3b, v58
	v_exp_f32_e32 v72, v72
	v_cvt_pk_bf16_f32 v70, v71, v69
	ds_read_b32 v71, v106 offset:4416
	global_store_dword v[104:105], v70, off offset:3136
	v_sub_f32_e32 v73, 1.0, v72
	v_add_f32_e32 v72, 1.0, v72
	v_mul_f32_e32 v72, v73, v72
	v_sqrt_f32_e32 v72, v72
	s_waitcnt lgkmcnt(0)
	v_mul_f32_e32 v54, v54, v71
	v_mul_f32_e32 v71, 0x3fb8aa3b, v59
	v_exp_f32_e32 v71, v71
	v_mul_f32_e32 v54, v72, v54
	v_cvt_pk_bf16_f32 v54, v58, v54
	ds_read_b32 v58, v106 offset:4688
	v_add_f32_e32 v55, 1.0, v55
	v_sub_f32_e32 v72, 1.0, v71
	v_add_f32_e32 v71, 1.0, v71
	v_rcp_f32_e32 v55, v55
	v_mul_f32_e32 v71, v72, v71
	v_sqrt_f32_e32 v71, v71
	global_store_dword v[74:75], v54, off offset:64
	s_waitcnt lgkmcnt(0)
	v_mul_f32_e32 v55, v55, v58
	v_exp_f32_e32 v56, v56
	v_mul_f32_e32 v55, v71, v55
	v_cvt_pk_bf16_f32 v55, v59, v55
	v_add_f32_e32 v59, v113, v60
	v_mul_f32_e32 v59, 0xbfb8aa3b, v59
	v_exp_f32_e32 v59, v59
	ds_read_b32 v58, v106 offset:4960
	v_add_f32_e32 v56, 1.0, v56
	v_rcp_f32_e32 v56, v56
	v_add_f32_e32 v59, 1.0, v59
	v_rcp_f32_e32 v59, v59
	global_store_dword v[74:75], v55, off offset:1088
	s_waitcnt lgkmcnt(0)
	v_mul_f32_e32 v56, v56, v58
	v_add_f32_e32 v57, v112, v57
	v_mul_f32_e32 v59, 0xc1000000, v59
	v_mul_f32_e32 v59, v63, v59
	v_mul_f32_e32 v60, 0x3fb8aa3b, v59
	v_exp_f32_e32 v60, v60
	v_mul_f32_e32 v57, 0xbfb8aa3b, v57
	v_exp_f32_e32 v57, v57
	v_lshlrev_b32_e32 v62, 16, v64
	v_sub_f32_e32 v71, 1.0, v60
	v_add_f32_e32 v60, 1.0, v60
	v_mul_f32_e32 v60, v71, v60
	v_sqrt_f32_e32 v60, v60
	v_add_f32_e32 v57, 1.0, v57
	v_lshlrev_b32_e32 v65, 16, v66
	v_lshlrev_b32_e32 v67, 16, v68
	v_mul_f32_e32 v56, v60, v56
	v_cvt_pk_bf16_f32 v56, v59, v56
	v_add_f32_e32 v59, v113, v61
	v_mul_f32_e32 v59, 0xbfb8aa3b, v59
	v_exp_f32_e32 v59, v59
	ds_read_b32 v58, v106 offset:5232
	v_rcp_f32_e32 v57, v57
	v_mul_f32_e32 v62, 0x3fb8aa3b, v62
	v_add_f32_e32 v59, 1.0, v59
	v_rcp_f32_e32 v59, v59
	v_mul_f32_e32 v65, 0x3fb8aa3b, v65
	v_mul_f32_e32 v67, 0x3fb8aa3b, v67
	v_exp_f32_e32 v62, v62
	v_mul_f32_e32 v59, 0xc1000000, v59
	v_mul_f32_e32 v59, v63, v59
	v_mul_f32_e32 v60, 0x3fb8aa3b, v59
	v_exp_f32_e32 v60, v60
	v_exp_f32_e32 v65, v65
	v_exp_f32_e32 v67, v67
	s_waitcnt lgkmcnt(0)
	v_mul_f32_e32 v57, v57, v58
	v_sub_f32_e32 v61, 1.0, v60
	v_add_f32_e32 v60, 1.0, v60
	v_mul_f32_e32 v60, v61, v60
	v_sqrt_f32_e32 v60, v60
	v_and_b32_e32 v64, 0xffff0000, v64
	v_and_b32_e32 v66, 0xffff0000, v66
	v_and_b32_e32 v68, 0xffff0000, v68
	v_and_b32_e32 v69, 0xffff0000, v70
	v_mul_f32_e32 v57, v60, v57
	s_and_b64 vcc, exec, s[38:39]
	global_store_dword v[74:75], v56, off offset:2112
	v_cvt_pk_bf16_f32 v58, v59, v57
	global_store_dword v[74:75], v58, off offset:3136
	s_cbranch_vccnz .LBB0_633
	v_fma_f32 v57, v67, v69, v68
	v_fma_f32 v57, v65, v57, v66
	v_fma_f32 v57, v62, v57, v64
	s_mov_b64 s[4:5], 0

; template <bool PASS2> ...
;     ...
;             for (int tb = 0; tb < 2; ++tb) {
;                 Ap[tb] = (av[tb][0] * av[tb][1]) * (av[tb][2] * av[tb][3]);
;                 Bp[tb] = d == 0 ? ((bv[tb][0] * av[tb][1] + bv[tb][1]) * av[tb][2] + bv[tb][2]) * av[tb][3] + bv[tb][3]
;                                 : ((bv[tb][3] * av[tb][2] + bv[tb][2]) * av[tb][1] + bv[tb][1]) * av[tb][0] + bv[tb][0];
;             }
;             float PA[8], PB[8];
; #pragma unroll
;             for (int e = 0; e < 8; ++e) { PA[e] = __shfl(Ap[e >> 2], (e & 3) * 16 + fr); PB[e] = __shfl(Bp[e >> 2], (e & 3) * 16 + fr); }
;             const size_t si = ((size_t)(b * NCH + c) * 2 + d) * 256 + chn;
;             if (!PASS2) {
;                 float At = 1.f, Bt = 0.f;
; #pragma unroll
;                 for (int e2 = 0; e2 < 8; ++e2) { const int e = d == 0 ? e2 : 7 - e2; Bt = PA[e] * Bt + PB[e]; At *= PA[e]; }
;                 if (fq == 0) { LRA[si] = At; LRB[si] = Bt; }
.LBB0_639:
	v_mul_f32_e32 v54, v61, v54
	v_mul_f32_e32 v55, v55, v66
	v_mul_f32_e32 v64, v54, v55
	v_mul_f32_e32 v54, v62, v65
	v_mul_f32_e32 v55, v67, v60
	v_or_b32_e32 v59, 64, v76
	v_or_b32_e32 v58, 0x80, v76
	v_mul_f32_e32 v60, v54, v55
	ds_bpermute_b32 v68, v76, v60
	ds_bpermute_b32 v54, v76, v57
	ds_bpermute_b32 v71, v59, v60
	ds_bpermute_b32 v55, v59, v57
	ds_bpermute_b32 v70, v58, v60
	ds_bpermute_b32 v56, v58, v57
	ds_bpermute_b32 v69, v77, v60
	ds_bpermute_b32 v57, v77, v57
	ds_bpermute_b32 v66, v76, v64
	ds_bpermute_b32 v63, v76, v72
	ds_bpermute_b32 v67, v59, v64
	ds_bpermute_b32 v62, v59, v72
	ds_bpermute_b32 v65, v58, v64
	ds_bpermute_b32 v61, v58, v72
	ds_bpermute_b32 v64, v77, v64
	ds_bpermute_b32 v60, v77, v72
	s_and_saveexec_b64 s[4:5], s[36:37]
	s_cbranch_execz .LBB0_641
	s_cmp_eq_u32 s64, 1
	s_cselect_b64 vcc, -1, 0
	s_cmp_eq_u32 s64, 2
	s_waitcnt lgkmcnt(0)
	v_cndmask_b32_e32 v78, v68, v71, vcc
	s_cselect_b64 vcc, -1, 0
	s_cmp_eq_u32 s64, 3
	v_cndmask_b32_e32 v78, v78, v70, vcc
	s_cselect_b64 vcc, -1, 0
	s_cmp_eq_u32 s64, 4
	v_cndmask_b32_e32 v78, v78, v69, vcc
	s_cselect_b64 vcc, -1, 0
	s_cmp_eq_u32 s64, 5
	v_cndmask_b32_e32 v78, v78, v66, vcc
	s_cselect_b64 vcc, -1, 0
	s_cmp_eq_u32 s64, 6
	v_cndmask_b32_e32 v78, v78, v67, vcc
	s_cselect_b64 vcc, -1, 0
	s_cmp_eq_u32 s64, 7
	v_cndmask_b32_e32 v78, v78, v65, vcc
	s_cselect_b64 vcc, -1, 0
	s_cmp_eq_u32 s62, 1
	v_cndmask_b32_e32 v78, v78, v64, vcc
	s_cselect_b64 vcc, -1, 0
	s_cmp_eq_u32 s62, 2
	v_cndmask_b32_e32 v79, v68, v71, vcc
	s_cselect_b64 vcc, -1, 0
	s_cmp_eq_u32 s62, 3
	v_cndmask_b32_e32 v79, v79, v70, vcc
	s_cselect_b64 vcc, -1, 0
	s_cmp_eq_u32 s62, 4
	v_cndmask_b32_e32 v79, v79, v69, vcc
	s_cselect_b64 vcc, -1, 0
	s_cmp_eq_u32 s62, 5
	v_cndmask_b32_e32 v79, v79, v66, vcc
	s_cselect_b64 vcc, -1, 0
	s_cmp_eq_u32 s62, 6
	v_cndmask_b32_e32 v79, v79, v67, vcc
	s_cselect_b64 vcc, -1, 0
	s_cmp_eq_u32 s62, 7
	v_cndmask_b32_e32 v79, v79, v65, vcc
	s_cselect_b64 vcc, -1, 0
	s_cmp_eq_u32 s60, 1
	v_cndmask_b32_e32 v79, v79, v64, vcc
	s_cselect_b64 vcc, -1, 0
	s_cmp_eq_u32 s60, 2
	v_cndmask_b32_e32 v81, v68, v71, vcc
	s_cselect_b64 vcc, -1, 0
	s_cmp_eq_u32 s60, 3
	v_cndmask_b32_e32 v81, v81, v70, vcc
	s_cselect_b64 vcc, -1, 0
	s_cmp_eq_u32 s60, 4
	v_cndmask_b32_e32 v81, v81, v69, vcc
	s_cselect_b64 vcc, -1, 0
	s_cmp_eq_u32 s60, 5
	v_cndmask_b32_e32 v81, v81, v66, vcc
	s_cselect_b64 vcc, -1, 0
	s_cmp_eq_u32 s60, 6
	v_cndmask_b32_e32 v81, v81, v67, vcc
	s_cselect_b64 vcc, -1, 0
	s_cmp_eq_u32 s60, 7
	v_cndmask_b32_e32 v81, v81, v65, vcc
	s_cselect_b64 vcc, -1, 0
	s_cmp_eq_u32 s58, 1
	v_cndmask_b32_e32 v81, v81, v64, vcc
	s_cselect_b64 vcc, -1, 0
	s_cmp_eq_u32 s58, 2
	v_cndmask_b32_e32 v82, v68, v71, vcc
	s_cselect_b64 vcc, -1, 0
	s_cmp_eq_u32 s58, 3
	v_cndmask_b32_e32 v82, v82, v70, vcc
	s_cselect_b64 vcc, -1, 0
	s_cmp_eq_u32 s58, 4
	v_cndmask_b32_e32 v82, v82, v69, vcc
	s_cselect_b64 vcc, -1, 0
	s_cmp_eq_u32 s58, 5
	v_cndmask_b32_e32 v82, v82, v66, vcc
	s_cselect_b64 vcc, -1, 0
	s_cmp_eq_u32 s58, 6
	v_cndmask_b32_e32 v82, v82, v67, vcc
	s_cselect_b64 vcc, -1, 0
	s_cmp_eq_u32 s58, 7
	v_cndmask_b32_e32 v82, v82, v65, vcc
	s_cselect_b64 vcc, -1, 0
	s_cmp_eq_u32 s56, 1
	v_cndmask_b32_e32 v82, v82, v64, vcc
	s_cselect_b64 vcc, -1, 0
	s_cmp_eq_u32 s56, 2
	v_cndmask_b32_e32 v83, v68, v71, vcc
	s_cselect_b64 vcc, -1, 0
	s_cmp_eq_u32 s56, 3
	v_cndmask_b32_e32 v83, v83, v70, vcc
	s_cselect_b64 vcc, -1, 0
	s_cmp_eq_u32 s56, 4
	v_cndmask_b32_e32 v83, v83, v69, vcc
	s_cselect_b64 vcc, -1, 0
	s_cmp_eq_u32 s56, 5
	v_cndmask_b32_e32 v83, v83, v66, vcc
	s_cselect_b64 vcc, -1, 0
	s_cmp_eq_u32 s56, 6
	v_cndmask_b32_e32 v83, v83, v67, vcc
	s_cselect_b64 vcc, -1, 0
	s_cmp_eq_u32 s56, 7
	v_cndmask_b32_e32 v83, v83, v65, vcc
	s_cselect_b64 vcc, -1, 0
	s_cmp_eq_u32 s54, 1
	v_cndmask_b32_e32 v83, v83, v64, vcc
	s_cselect_b64 vcc, -1, 0
	s_cmp_eq_u32 s54, 2
	v_cndmask_b32_e32 v84, v68, v71, vcc
	s_cselect_b64 vcc, -1, 0
	s_cmp_eq_u32 s54, 3
	v_cndmask_b32_e32 v84, v84, v70, vcc
	s_cselect_b64 vcc, -1, 0
	s_cmp_eq_u32 s54, 4
	v_cndmask_b32_e32 v84, v84, v69, vcc
	s_cselect_b64 vcc, -1, 0
	s_cmp_eq_u32 s54, 5
	v_cndmask_b32_e32 v84, v84, v66, vcc
	s_cselect_b64 vcc, -1, 0
	s_cmp_eq_u32 s54, 6
	v_cndmask_b32_e32 v84, v84, v67, vcc
	s_cselect_b64 vcc, -1, 0
	s_cmp_eq_u32 s54, 7
	v_cndmask_b32_e32 v84, v84, v65, vcc
	s_cselect_b64 vcc, -1, 0
	s_cmp_eq_u32 s52, 1
	v_cndmask_b32_e32 v84, v84, v64, vcc
	s_cselect_b64 vcc, -1, 0
	s_cmp_eq_u32 s52, 2
	v_cndmask_b32_e32 v85, v68, v71, vcc
	s_cselect_b64 vcc, -1, 0
	s_cmp_eq_u32 s52, 3
	v_cndmask_b32_e32 v85, v85, v70, vcc
	s_cselect_b64 vcc, -1, 0
	s_cmp_eq_u32 s52, 4
	v_cndmask_b32_e32 v85, v85, v69, vcc
	s_cselect_b64 vcc, -1, 0
	s_cmp_eq_u32 s52, 5
	v_cndmask_b32_e32 v85, v85, v66, vcc
	s_cselect_b64 vcc, -1, 0
	s_cmp_eq_u32 s52, 6
	v_cndmask_b32_e32 v85, v85, v67, vcc
	s_cselect_b64 vcc, -1, 0
	s_cmp_eq_u32 s52, 7
	v_cndmask_b32_e32 v85, v85, v65, vcc
	s_cselect_b64 vcc, -1, 0
	s_cmp_eq_u32 s50, 1
	v_cndmask_b32_e32 v85, v85, v64, vcc
	s_cselect_b64 vcc, -1, 0
	s_cmp_eq_u32 s50, 2
	v_cndmask_b32_e32 v68, v68, v71, vcc
	s_cselect_b64 vcc, -1, 0
	s_cmp_eq_u32 s50, 3
	v_cndmask_b32_e32 v68, v68, v70, vcc
	s_cselect_b64 vcc, -1, 0
	s_cmp_eq_u32 s50, 4
	v_cndmask_b32_e32 v68, v68, v69, vcc
	s_cselect_b64 vcc, -1, 0
	s_cmp_eq_u32 s50, 5
	v_cndmask_b32_e32 v66, v68, v66, vcc
	s_cselect_b64 vcc, -1, 0
	s_cmp_eq_u32 s50, 6
	v_cndmask_b32_e32 v66, v66, v67, vcc
	s_cselect_b64 vcc, -1, 0
	v_cndmask_b32_e32 v65, v66, v65, vcc
	v_cndmask_b32_e64 v66, v60, v54, s[48:49]
	v_fmac_f32_e32 v66, 0, v78
	v_cndmask_b32_e64 v67, v61, v55, s[48:49]
	v_fmac_f32_e32 v67, v79, v66
	v_cndmask_b32_e64 v66, v62, v56, s[48:49]
	v_mul_f32_e32 v80, v78, v79
	v_fmac_f32_e32 v66, v81, v67
	v_cndmask_b32_e64 v67, v63, v57, s[48:49]
	v_mul_f32_e32 v80, v81, v80
	v_fmac_f32_e32 v67, v82, v66
	v_cndmask_b32_e64 v57, v57, v63, s[48:49]
	v_mul_f32_e32 v80, v82, v80
	s_cmp_eq_u32 s50, 7
	v_fmac_f32_e32 v57, v83, v67
	v_cndmask_b32_e64 v56, v56, v62, s[48:49]
	v_mul_f32_e32 v80, v83, v80
	s_cselect_b64 vcc, -1, 0
	v_fmac_f32_e32 v56, v84, v57
	v_cndmask_b32_e64 v55, v55, v61, s[48:49]
	v_mov_b32_e32 v73, s67
	v_or_b32_e32 v72, s66, v96
	v_mul_f32_e32 v80, v84, v80
	v_cndmask_b32_e32 v64, v65, v64, vcc
	v_fmac_f32_e32 v55, v85, v56
	v_cndmask_b32_e64 v60, v54, v60, s[48:49]
	v_mul_f32_e32 v80, v85, v80
	v_fmac_f32_e32 v60, v64, v55
	v_lshlrev_b64 v[54:55], 2, v[72:73]
	v_mul_f32_e32 v65, v64, v80
	v_lshl_add_u64 v[56:57], s[44:45], 0, v[54:55]
	v_lshl_add_u64 v[54:55], s[42:43], 0, v[54:55]
	global_store_dword v[54:55], v65, off
	global_store_dword v[56:57], v60, off
; __device__ __forceinline__ float sigm(float x) { return __builtin_amdgcn_rcpf(1.f + __expf(-x)); }
; #define MFMA16(a, b, c) __builtin_amdgcn_mfma_f32_16x16x32_bf16((a), (b), (c), 0, 0, 0)
; template <bool PASS2> ...
;     ...
;                 for (int ks = 0; ks < 2; ++ks) {
; #pragma unroll
;                     for (int tb = 0; tb < 2; ++tb) { ga[tb] = MFMA16(af[tb][ks], wfa[cb][ks], ga[tb]); gx[tb] = MFMA16(af[tb][ks], wfx[cb][ks], gx[tb]); } }
;                 const float ba = pba[cb], bx = pbx[cb], sp = log1pf(__expf(-plm[cb]));
; #pragma unroll
;                 for (int tb = 0; tb < 2; ++tb)
; #pragma unroll
;                     for (int q = 0; q < 4; ++q) { const float xv = xl[(tb * 16 + fq * 4 + q) * 68 + cb * 16 + fr];
;                         const float r = sigm(ga[tb][q] + ba), ig = sigm(gx[tb][q] + bx), la = -8.f * r * sp;
;                         const float aa = __expf(la), om = (1.f - aa) * (1.f + aa), bb = __builtin_amdgcn_sqrtf(om) * (ig * xv);
.LBB0_641:
	s_or_b64 exec, exec, s[4:5]
	s_waitcnt lgkmcnt(0)
	v_mfma_f32_16x16x32_bf16 v[54:57], v[2:5], v[46:49], 0
	s_mov_b64 s[4:5], -1
	v_mfma_f32_16x16x32_bf16 v[60:63], v[2:5], v[50:53], 0
	v_mfma_f32_16x16x32_bf16 v[46:49], v[14:17], v[46:49], 0
	v_mfma_f32_16x16x32_bf16 v[64:67], v[14:17], v[50:53], 0
	v_mfma_f32_16x16x32_bf16 v[54:57], v[6:9], v[38:41], v[54:57]
	v_mfma_f32_16x16x32_bf16 v[50:53], v[6:9], v[42:45], v[60:63]
	v_mfma_f32_16x16x32_bf16 v[46:49], v[18:21], v[38:41], v[46:49]
	v_mfma_f32_16x16x32_bf16 v[38:41], v[18:21], v[42:45], v[64:67]
	v_mul_f32_e32 v42, 0xbfb8aa3b, v111
	v_exp_f32_e32 v44, v42
	s_nop 3
	v_add_f32_e32 v51, v109, v51
	v_mul_f32_e32 v51, 0xbfb8aa3b, v51
	v_exp_f32_e32 v51, v51
	v_add_f32_e32 v45, 1.0, v44
	v_add_f32_e32 v42, -1.0, v45
	v_sub_f32_e32 v43, v42, v45
	v_add_f32_e32 v43, 1.0, v43
	v_sub_f32_e32 v42, v44, v42
	v_add_f32_e32 v60, v42, v43
	v_frexp_mant_f32_e32 v42, v45
	v_cmp_gt_f32_e32 vcc, s70, v42
	v_cvt_f64_f32_e32 v[42:43], v45
	v_frexp_exp_i32_f64_e32 v42, v[42:43]
	v_subbrev_co_u32_e32 v42, vcc, 0, v42, vcc
	v_sub_u32_e32 v43, 0, v42
	v_ldexp_f32 v45, v45, v43
	v_ldexp_f32 v43, v60, v43
	v_add_f32_e32 v60, -1.0, v45
	v_add_f32_e32 v61, 1.0, v60
	v_sub_f32_e32 v61, v45, v61
	v_add_f32_e32 v61, v43, v61
	v_add_f32_e32 v62, v60, v61
	v_sub_f32_e32 v60, v62, v60
	v_sub_f32_e32 v60, v61, v60
	v_add_f32_e32 v61, 1.0, v45
	v_add_f32_e32 v63, -1.0, v61
	v_sub_f32_e32 v45, v45, v63
	v_add_f32_e32 v43, v43, v45
	v_add_f32_e32 v45, v61, v43
	v_sub_f32_e32 v61, v45, v61
	v_sub_f32_e32 v43, v43, v61
	v_rcp_f32_e32 v61, v45
	v_cvt_f32_i32_e32 v42, v42
	v_cmp_neq_f32_e32 vcc, s12, v44
	v_add_f32_e32 v51, 1.0, v51
	v_mul_f32_e32 v63, v62, v61
	v_mul_f32_e32 v64, v45, v63
	v_fma_f32 v65, v63, v45, -v64
	v_fmac_f32_e32 v65, v63, v43
	v_add_f32_e32 v66, v64, v65
	v_sub_f32_e32 v67, v62, v66
	v_sub_f32_e32 v62, v62, v67
	v_sub_f32_e32 v64, v66, v64
	v_sub_f32_e32 v62, v62, v66
	v_add_f32_e32 v60, v60, v62
	v_sub_f32_e32 v62, v64, v65
	v_add_f32_e32 v60, v62, v60
	v_add_f32_e32 v62, v67, v60
	v_mul_f32_e32 v64, v61, v62
	v_mul_f32_e32 v65, v45, v64
	v_fma_f32 v45, v64, v45, -v65
	v_fmac_f32_e32 v45, v64, v43
	v_sub_f32_e32 v43, v67, v62
	v_add_f32_e32 v43, v60, v43
	v_add_f32_e32 v60, v65, v45
	v_sub_f32_e32 v66, v62, v60
	v_sub_f32_e32 v62, v62, v66
	v_sub_f32_e32 v65, v60, v65
	v_sub_f32_e32 v60, v62, v60
	v_add_f32_e32 v43, v43, v60
	v_sub_f32_e32 v45, v65, v45
	v_add_f32_e32 v43, v45, v43
	v_add_f32_e32 v45, v63, v64
	v_add_f32_e32 v43, v66, v43
	v_sub_f32_e32 v60, v45, v63
	v_mul_f32_e32 v43, v61, v43
	v_sub_f32_e32 v60, v64, v60
	v_add_f32_e32 v43, v60, v43
	v_mul_f32_e32 v63, 0x3f317218, v42
	v_add_f32_e32 v60, v45, v43
	v_fma_f32 v64, v42, s71, -v63
	v_mul_f32_e32 v61, v60, v60
	v_fmac_f32_e32 v64, 0xb102e308, v42
	v_sub_f32_e32 v42, v60, v45
	v_fmamk_f32 v62, v61, 0x3e9b6dac, v198
	v_sub_f32_e32 v42, v43, v42
	v_add_f32_e32 v43, v63, v64
	v_fmaak_f32 v62, v61, v62, 0x3f2aaada
	v_sub_f32_e32 v45, v43, v63
	v_ldexp_f32 v63, v60, 1
	v_mul_f32_e32 v60, v60, v61
	v_mul_f32_e32 v60, v60, v62
	v_add_f32_e32 v61, v63, v60
	v_sub_f32_e32 v62, v61, v63
	v_ldexp_f32 v42, v42, 1
	v_sub_f32_e32 v60, v60, v62
	v_add_f32_e32 v42, v42, v60
	v_add_f32_e32 v60, v61, v42
	v_sub_f32_e32 v61, v60, v61
	v_sub_f32_e32 v42, v42, v61
	v_add_f32_e32 v61, v43, v60
	v_sub_f32_e32 v62, v61, v43
	v_sub_f32_e32 v63, v61, v62
	v_sub_f32_e32 v45, v64, v45
	v_sub_f32_e32 v43, v43, v63
	v_sub_f32_e32 v60, v60, v62
	v_add_f32_e32 v43, v60, v43
	v_add_f32_e32 v60, v45, v42
	v_sub_f32_e32 v62, v60, v45
	v_sub_f32_e32 v63, v60, v62
	v_sub_f32_e32 v45, v45, v63
	v_sub_f32_e32 v42, v42, v62
	v_add_f32_e32 v43, v60, v43
	v_add_f32_e32 v42, v42, v45
	v_add_f32_e32 v45, v61, v43
	v_sub_f32_e32 v60, v45, v61
	v_sub_f32_e32 v43, v43, v60
	v_add_f32_e32 v42, v42, v43
	v_add_f32_e32 v42, v45, v42
	v_cndmask_b32_e32 v42, v203, v42, vcc
	v_cmp_ngt_f32_e32 vcc, -1.0, v44
	v_add_f32_e32 v45, v109, v50
	v_mul_f32_e32 v45, 0xbfb8aa3b, v45
	v_cndmask_b32_e32 v42, v204, v42, vcc
	v_cmp_neq_f32_e32 vcc, -1.0, v44
	v_exp_f32_e32 v45, v45
	v_rcp_f32_e32 v51, v51
	v_cndmask_b32_e32 v42, v205, v42, vcc
	v_cmp_lt_f32_e64 vcc, |v44|, s13
	v_add_f32_e32 v45, 1.0, v45
	v_rcp_f32_e32 v45, v45
	v_cndmask_b32_e32 v43, v42, v44, vcc
	v_add_f32_e32 v44, v110, v54
	v_mul_f32_e32 v44, 0xbfb8aa3b, v44
	v_exp_f32_e32 v44, v44
	ds_read_b32 v42, v106 offset:128
	v_add_f32_e32 v52, v109, v52
	v_mul_f32_e32 v52, 0xbfb8aa3b, v52
	v_add_f32_e32 v44, 1.0, v44
	v_rcp_f32_e32 v44, v44
	s_waitcnt lgkmcnt(0)
	v_mul_f32_e32 v42, v42, v45
	v_exp_f32_e32 v52, v52
	v_add_f32_e32 v46, v110, v46
	v_mul_f32_e32 v44, 0xc1000000, v44
	v_mul_f32_e32 v44, v43, v44
	v_mul_f32_e32 v50, 0x3fb8aa3b, v44
	v_exp_f32_e32 v50, v50
	v_add_f32_e32 v52, 1.0, v52
	v_rcp_f32_e32 v52, v52
	v_add_f32_e32 v53, v109, v53
	v_sub_f32_e32 v54, 1.0, v50
	v_add_f32_e32 v50, 1.0, v50
	v_mul_f32_e32 v50, v54, v50
	v_sqrt_f32_e32 v50, v50
	v_mul_f32_e32 v46, 0xbfb8aa3b, v46
	v_mul_f32_e32 v53, 0xbfb8aa3b, v53
	v_exp_f32_e32 v46, v46
	v_mul_f32_e32 v42, v42, v50
	v_add_f32_e32 v50, v110, v55
	v_mul_f32_e32 v50, 0xbfb8aa3b, v50
	v_exp_f32_e32 v50, v50
	v_cvt_pk_bf16_f32 v44, v44, v42
	ds_read_b32 v45, v106 offset:400
	global_store_dword v[104:105], v44, off offset:128
	v_add_f32_e32 v50, 1.0, v50
	v_rcp_f32_e32 v50, v50
	v_exp_f32_e32 v53, v53
	s_waitcnt lgkmcnt(0)
; __device__ __forceinline__ unsigned cvt_pk_bf16(float lo, float hi) { unsigned r; asm volatile("v_cvt_pk_bf16_f32 %0, %1, %2" : "=v"(r) : "v"(lo), "v"(hi)); return r; }
; __device__ __forceinline__ float bflo(unsigned w) { return __uint_as_float(w << 16); }
; __device__ __forceinline__ float bfhi(unsigned w) { return __uint_as_float(w & 0xffff0000u); }
; __device__ __forceinline__ float sigm(float x) { return __builtin_amdgcn_rcpf(1.f + __expf(-x)); }
; template <bool PASS2> ...
;     ...
;                     for (int q = 0; q < 4; ++q) { const float xv = xl[(tb * 16 + fq * 4 + q) * 68 + cb * 16 + fr];
;                         const float r = sigm(ga[tb][q] + ba), ig = sigm(gx[tb][q] + bx), la = -8.f * r * sp;
;                         const float aa = __expf(la), om = (1.f - aa) * (1.f + aa), bb = __builtin_amdgcn_sqrtf(om) * (ig * xv);
;                         const unsigned pk = cvt_pk_bf16(la, bb);
;                         labd[(size_t)(tb * 16 + q) * 256 + cb * 16] = pk;
;                         av[tb][q] = __expf(bflo(pk)); bv[tb][q] = bfhi(pk); }
	v_mul_f32_e32 v45, v51, v45
	v_add_f32_e32 v46, 1.0, v46
	v_mul_f32_e32 v50, 0xc1000000, v50
	v_mul_f32_e32 v50, v43, v50
	v_mul_f32_e32 v54, 0x3fb8aa3b, v50
	v_exp_f32_e32 v54, v54
	v_add_f32_e32 v53, 1.0, v53
	v_rcp_f32_e32 v46, v46
	v_add_f32_e32 v47, v110, v47
	v_sub_f32_e32 v55, 1.0, v54
	v_add_f32_e32 v54, 1.0, v54
	v_mul_f32_e32 v54, v55, v54
	v_sqrt_f32_e32 v54, v54
	v_rcp_f32_e32 v53, v53
	v_mul_f32_e32 v47, 0xbfb8aa3b, v47
	v_add_f32_e32 v38, v109, v38
	v_mul_f32_e32 v45, v45, v54
	v_add_f32_e32 v54, v110, v56
	v_mul_f32_e32 v54, 0xbfb8aa3b, v54
	v_exp_f32_e32 v54, v54
	v_cvt_pk_bf16_f32 v50, v50, v45
	ds_read_b32 v51, v106 offset:672
	global_store_dword v[104:105], v50, off offset:1152
	v_add_f32_e32 v54, 1.0, v54
	v_rcp_f32_e32 v54, v54
	v_exp_f32_e32 v47, v47
	s_waitcnt lgkmcnt(0)
	v_mul_f32_e32 v51, v52, v51
	v_mul_f32_e32 v38, 0xbfb8aa3b, v38
	v_mul_f32_e32 v54, 0xc1000000, v54
	v_mul_f32_e32 v54, v43, v54
	v_mul_f32_e32 v55, 0x3fb8aa3b, v54
	v_exp_f32_e32 v55, v55
	v_exp_f32_e32 v38, v38
	v_mul_f32_e32 v46, 0xc1000000, v46
	v_mul_f32_e32 v46, v43, v46
	v_sub_f32_e32 v56, 1.0, v55
	v_add_f32_e32 v55, 1.0, v55
	v_mul_f32_e32 v55, v56, v55
	v_sqrt_f32_e32 v55, v55
	v_add_f32_e32 v47, 1.0, v47
	v_rcp_f32_e32 v47, v47
	v_add_f32_e32 v38, 1.0, v38
	v_mul_f32_e32 v51, v51, v55
	v_add_f32_e32 v55, v110, v57
	v_mul_f32_e32 v55, 0xbfb8aa3b, v55
	v_exp_f32_e32 v55, v55
	v_cvt_pk_bf16_f32 v52, v54, v51
	ds_read_b32 v54, v106 offset:944
	global_store_dword v[104:105], v52, off offset:2176
	v_add_f32_e32 v55, 1.0, v55
	v_rcp_f32_e32 v55, v55
	v_rcp_f32_e32 v38, v38
	s_waitcnt lgkmcnt(0)
	v_mul_f32_e32 v53, v53, v54
	v_mul_f32_e32 v47, 0xc1000000, v47
	v_mul_f32_e32 v55, 0xc1000000, v55
	v_mul_f32_e32 v55, v43, v55
	v_mul_f32_e32 v56, 0x3fb8aa3b, v55
	v_exp_f32_e32 v56, v56
	v_add_f32_e32 v39, v109, v39
	v_mul_f32_e32 v47, v43, v47
	v_mul_f32_e32 v39, 0xbfb8aa3b, v39
	v_sub_f32_e32 v57, 1.0, v56
	v_add_f32_e32 v56, 1.0, v56
	v_mul_f32_e32 v56, v57, v56
	v_sqrt_f32_e32 v56, v56
	v_exp_f32_e32 v39, v39
	v_add_f32_e32 v40, v109, v40
	v_mul_f32_e32 v40, 0xbfb8aa3b, v40
	v_mul_f32_e32 v53, v56, v53
	v_mul_f32_e32 v56, 0x3fb8aa3b, v46
	v_exp_f32_e32 v56, v56
	v_cvt_pk_bf16_f32 v54, v55, v53
	ds_read_b32 v55, v106 offset:4480
	global_store_dword v[104:105], v54, off offset:3200
	v_sub_f32_e32 v57, 1.0, v56
	v_add_f32_e32 v56, 1.0, v56
	v_mul_f32_e32 v56, v57, v56
	v_sqrt_f32_e32 v56, v56
	s_waitcnt lgkmcnt(0)
	v_mul_f32_e32 v38, v38, v55
	v_mul_f32_e32 v55, 0x3fb8aa3b, v47
	v_exp_f32_e32 v55, v55
	v_mul_f32_e32 v38, v56, v38
	v_cvt_pk_bf16_f32 v38, v46, v38
	ds_read_b32 v46, v106 offset:4752
	v_add_f32_e32 v39, 1.0, v39
	v_sub_f32_e32 v56, 1.0, v55
	v_add_f32_e32 v55, 1.0, v55
	v_rcp_f32_e32 v39, v39
	v_mul_f32_e32 v55, v56, v55
	v_sqrt_f32_e32 v55, v55
	global_store_dword v[74:75], v38, off offset:128
	s_waitcnt lgkmcnt(0)
	v_mul_f32_e32 v39, v39, v46
	v_exp_f32_e32 v40, v40
	v_mul_f32_e32 v39, v55, v39
	v_cvt_pk_bf16_f32 v39, v47, v39
	v_add_f32_e32 v47, v110, v48
	v_mul_f32_e32 v47, 0xbfb8aa3b, v47
	v_exp_f32_e32 v47, v47
	ds_read_b32 v46, v106 offset:5024
	v_add_f32_e32 v40, 1.0, v40
	v_rcp_f32_e32 v40, v40
	v_add_f32_e32 v47, 1.0, v47
	v_rcp_f32_e32 v47, v47
	global_store_dword v[74:75], v39, off offset:1152
	s_waitcnt lgkmcnt(0)
	v_mul_f32_e32 v40, v40, v46
	v_add_f32_e32 v41, v109, v41
	v_mul_f32_e32 v47, 0xc1000000, v47
	v_mul_f32_e32 v47, v43, v47
	v_mul_f32_e32 v48, 0x3fb8aa3b, v47
	v_exp_f32_e32 v48, v48
	v_mul_f32_e32 v41, 0xbfb8aa3b, v41
	v_exp_f32_e32 v41, v41
	v_lshlrev_b32_e32 v42, 16, v44
	v_sub_f32_e32 v55, 1.0, v48
	v_add_f32_e32 v48, 1.0, v48
	v_mul_f32_e32 v48, v55, v48
	v_sqrt_f32_e32 v48, v48
	v_add_f32_e32 v41, 1.0, v41
	v_lshlrev_b32_e32 v45, 16, v50
	v_lshlrev_b32_e32 v51, 16, v52
	v_mul_f32_e32 v40, v48, v40
	v_cvt_pk_bf16_f32 v40, v47, v40
	v_add_f32_e32 v47, v110, v49
	v_mul_f32_e32 v47, 0xbfb8aa3b, v47
	v_exp_f32_e32 v47, v47
	ds_read_b32 v46, v106 offset:5296
	v_rcp_f32_e32 v41, v41
	v_mul_f32_e32 v42, 0x3fb8aa3b, v42
	v_add_f32_e32 v47, 1.0, v47
	v_rcp_f32_e32 v47, v47
	v_mul_f32_e32 v45, 0x3fb8aa3b, v45
	v_mul_f32_e32 v51, 0x3fb8aa3b, v51
	v_exp_f32_e32 v42, v42
	v_mul_f32_e32 v47, 0xc1000000, v47
	v_mul_f32_e32 v43, v43, v47
	v_mul_f32_e32 v47, 0x3fb8aa3b, v43
	v_exp_f32_e32 v47, v47
	v_exp_f32_e32 v45, v45
	v_exp_f32_e32 v51, v51
	s_waitcnt lgkmcnt(0)
	v_mul_f32_e32 v41, v41, v46
	v_sub_f32_e32 v48, 1.0, v47
	v_add_f32_e32 v47, 1.0, v47
	v_mul_f32_e32 v47, v48, v47
	v_sqrt_f32_e32 v47, v47
	v_and_b32_e32 v44, 0xffff0000, v44
	v_and_b32_e32 v50, 0xffff0000, v50
	v_and_b32_e32 v52, 0xffff0000, v52
	v_and_b32_e32 v53, 0xffff0000, v54
	v_mul_f32_e32 v41, v47, v41
	s_and_b64 vcc, exec, s[38:39]
	global_store_dword v[74:75], v40, off offset:2176
	v_cvt_pk_bf16_f32 v43, v43, v41
	global_store_dword v[74:75], v43, off offset:3200
	s_cbranch_vccnz .LBB0_643
	v_fma_f32 v41, v51, v53, v52
	v_fma_f32 v41, v45, v41, v50
	v_fma_f32 v41, v42, v41, v44
	s_mov_b64 s[4:5], 0

; template <bool PASS2> ...
;     ...
;             for (int tb = 0; tb < 2; ++tb) {
;                 Ap[tb] = (av[tb][0] * av[tb][1]) * (av[tb][2] * av[tb][3]);
;                 Bp[tb] = d == 0 ? ((bv[tb][0] * av[tb][1] + bv[tb][1]) * av[tb][2] + bv[tb][2]) * av[tb][3] + bv[tb][3]
;                                 : ((bv[tb][3] * av[tb][2] + bv[tb][2]) * av[tb][1] + bv[tb][1]) * av[tb][0] + bv[tb][0];
;             }
;             float PA[8], PB[8];
; #pragma unroll
;             for (int e = 0; e < 8; ++e) { PA[e] = __shfl(Ap[e >> 2], (e & 3) * 16 + fr); PB[e] = __shfl(Bp[e >> 2], (e & 3) * 16 + fr); }
;             const size_t si = ((size_t)(b * NCH + c) * 2 + d) * 256 + chn;
;             if (!PASS2) {
;                 float At = 1.f, Bt = 0.f;
; #pragma unroll
;                 for (int e2 = 0; e2 < 8; ++e2) { const int e = d == 0 ? e2 : 7 - e2; Bt = PA[e] * Bt + PB[e]; At *= PA[e]; }
;                 if (fq == 0) { LRA[si] = At; LRB[si] = Bt; }
.LBB0_649:
	v_mul_f32_e32 v38, v44, v38
	v_mul_f32_e32 v39, v39, v43
	v_mul_f32_e32 v55, v38, v39
	v_mul_f32_e32 v38, v42, v45
	v_mul_f32_e32 v39, v51, v46
	v_mul_f32_e32 v42, v38, v39
	ds_bpermute_b32 v50, v76, v42
	ds_bpermute_b32 v38, v76, v41
	ds_bpermute_b32 v53, v59, v42
	ds_bpermute_b32 v39, v59, v41
	ds_bpermute_b32 v52, v58, v42
	ds_bpermute_b32 v40, v58, v41
	ds_bpermute_b32 v51, v77, v42
	ds_bpermute_b32 v41, v77, v41
	ds_bpermute_b32 v48, v76, v55
	ds_bpermute_b32 v45, v76, v54
	ds_bpermute_b32 v49, v59, v55
	ds_bpermute_b32 v44, v59, v54
	ds_bpermute_b32 v47, v58, v55
	ds_bpermute_b32 v43, v58, v54
	ds_bpermute_b32 v46, v77, v55
	ds_bpermute_b32 v42, v77, v54
	s_and_saveexec_b64 s[4:5], s[36:37]
	s_cbranch_execz .LBB0_651
	s_cmp_eq_u32 s64, 1
	s_cselect_b64 vcc, -1, 0
	s_cmp_eq_u32 s64, 2
	s_waitcnt lgkmcnt(0)
	v_cndmask_b32_e32 v56, v50, v53, vcc
	s_cselect_b64 vcc, -1, 0
	s_cmp_eq_u32 s64, 3
	v_cndmask_b32_e32 v56, v56, v52, vcc
	s_cselect_b64 vcc, -1, 0
	s_cmp_eq_u32 s64, 4
	v_cndmask_b32_e32 v56, v56, v51, vcc
	s_cselect_b64 vcc, -1, 0
	s_cmp_eq_u32 s64, 5
	v_cndmask_b32_e32 v56, v56, v48, vcc
	s_cselect_b64 vcc, -1, 0
	s_cmp_eq_u32 s64, 6
	v_cndmask_b32_e32 v56, v56, v49, vcc
	s_cselect_b64 vcc, -1, 0
	s_cmp_eq_u32 s64, 7
	v_cndmask_b32_e32 v56, v56, v47, vcc
	s_cselect_b64 vcc, -1, 0
	s_cmp_eq_u32 s62, 1
	v_cndmask_b32_e32 v56, v56, v46, vcc
	s_cselect_b64 vcc, -1, 0
	s_cmp_eq_u32 s62, 2
	v_cndmask_b32_e32 v57, v50, v53, vcc
	s_cselect_b64 vcc, -1, 0
	s_cmp_eq_u32 s62, 3
	v_cndmask_b32_e32 v57, v57, v52, vcc
	s_cselect_b64 vcc, -1, 0
	s_cmp_eq_u32 s62, 4
	v_cndmask_b32_e32 v57, v57, v51, vcc
	s_cselect_b64 vcc, -1, 0
	s_cmp_eq_u32 s62, 5
	v_cndmask_b32_e32 v57, v57, v48, vcc
	s_cselect_b64 vcc, -1, 0
	s_cmp_eq_u32 s62, 6
	v_cndmask_b32_e32 v57, v57, v49, vcc
	s_cselect_b64 vcc, -1, 0
	s_cmp_eq_u32 s62, 7
	v_cndmask_b32_e32 v57, v57, v47, vcc
	s_cselect_b64 vcc, -1, 0
	s_cmp_eq_u32 s60, 1
	v_cndmask_b32_e32 v57, v57, v46, vcc
	s_cselect_b64 vcc, -1, 0
	s_cmp_eq_u32 s60, 2
	v_cndmask_b32_e32 v61, v50, v53, vcc
	s_cselect_b64 vcc, -1, 0
	s_cmp_eq_u32 s60, 3
	v_cndmask_b32_e32 v61, v61, v52, vcc
	s_cselect_b64 vcc, -1, 0
	s_cmp_eq_u32 s60, 4
	v_cndmask_b32_e32 v61, v61, v51, vcc
	s_cselect_b64 vcc, -1, 0
	s_cmp_eq_u32 s60, 5
	v_cndmask_b32_e32 v61, v61, v48, vcc
	s_cselect_b64 vcc, -1, 0
	s_cmp_eq_u32 s60, 6
	v_cndmask_b32_e32 v61, v61, v49, vcc
	s_cselect_b64 vcc, -1, 0
	s_cmp_eq_u32 s60, 7
	v_cndmask_b32_e32 v61, v61, v47, vcc
	s_cselect_b64 vcc, -1, 0
	s_cmp_eq_u32 s58, 1
	v_cndmask_b32_e32 v61, v61, v46, vcc
	s_cselect_b64 vcc, -1, 0
	s_cmp_eq_u32 s58, 2
	v_cndmask_b32_e32 v62, v50, v53, vcc
	s_cselect_b64 vcc, -1, 0
	s_cmp_eq_u32 s58, 3
	v_cndmask_b32_e32 v62, v62, v52, vcc
	s_cselect_b64 vcc, -1, 0
	s_cmp_eq_u32 s58, 4
	v_cndmask_b32_e32 v62, v62, v51, vcc
	s_cselect_b64 vcc, -1, 0
	s_cmp_eq_u32 s58, 5
	v_cndmask_b32_e32 v62, v62, v48, vcc
	s_cselect_b64 vcc, -1, 0
	s_cmp_eq_u32 s58, 6
	v_cndmask_b32_e32 v62, v62, v49, vcc
	s_cselect_b64 vcc, -1, 0
	s_cmp_eq_u32 s58, 7
	v_cndmask_b32_e32 v62, v62, v47, vcc
	s_cselect_b64 vcc, -1, 0
	s_cmp_eq_u32 s56, 1
	v_cndmask_b32_e32 v62, v62, v46, vcc
	s_cselect_b64 vcc, -1, 0
	s_cmp_eq_u32 s56, 2
	v_cndmask_b32_e32 v63, v50, v53, vcc
	s_cselect_b64 vcc, -1, 0
	s_cmp_eq_u32 s56, 3
	v_cndmask_b32_e32 v63, v63, v52, vcc
	s_cselect_b64 vcc, -1, 0
	s_cmp_eq_u32 s56, 4
	v_cndmask_b32_e32 v63, v63, v51, vcc
	s_cselect_b64 vcc, -1, 0
	s_cmp_eq_u32 s56, 5
	v_cndmask_b32_e32 v63, v63, v48, vcc
	s_cselect_b64 vcc, -1, 0
	s_cmp_eq_u32 s56, 6
	v_cndmask_b32_e32 v63, v63, v49, vcc
	s_cselect_b64 vcc, -1, 0
	s_cmp_eq_u32 s56, 7
	v_cndmask_b32_e32 v63, v63, v47, vcc
	s_cselect_b64 vcc, -1, 0
	s_cmp_eq_u32 s54, 1
	v_cndmask_b32_e32 v63, v63, v46, vcc
	s_cselect_b64 vcc, -1, 0
	s_cmp_eq_u32 s54, 2
	v_cndmask_b32_e32 v64, v50, v53, vcc
	s_cselect_b64 vcc, -1, 0
	s_cmp_eq_u32 s54, 3
	v_cndmask_b32_e32 v64, v64, v52, vcc
	s_cselect_b64 vcc, -1, 0
	s_cmp_eq_u32 s54, 4
	v_cndmask_b32_e32 v64, v64, v51, vcc
	s_cselect_b64 vcc, -1, 0
	s_cmp_eq_u32 s54, 5
	v_cndmask_b32_e32 v64, v64, v48, vcc
	s_cselect_b64 vcc, -1, 0
	s_cmp_eq_u32 s54, 6
	v_cndmask_b32_e32 v64, v64, v49, vcc
	s_cselect_b64 vcc, -1, 0
	s_cmp_eq_u32 s54, 7
	v_cndmask_b32_e32 v64, v64, v47, vcc
	s_cselect_b64 vcc, -1, 0
	s_cmp_eq_u32 s52, 1
	v_cndmask_b32_e32 v64, v64, v46, vcc
	s_cselect_b64 vcc, -1, 0
	s_cmp_eq_u32 s52, 2
	v_cndmask_b32_e32 v65, v50, v53, vcc
	s_cselect_b64 vcc, -1, 0
	s_cmp_eq_u32 s52, 3
	v_cndmask_b32_e32 v65, v65, v52, vcc
	s_cselect_b64 vcc, -1, 0
	s_cmp_eq_u32 s52, 4
	v_cndmask_b32_e32 v65, v65, v51, vcc
	s_cselect_b64 vcc, -1, 0
	s_cmp_eq_u32 s52, 5
	v_cndmask_b32_e32 v65, v65, v48, vcc
	s_cselect_b64 vcc, -1, 0
	s_cmp_eq_u32 s52, 6
	v_cndmask_b32_e32 v65, v65, v49, vcc
	s_cselect_b64 vcc, -1, 0
	s_cmp_eq_u32 s52, 7
	v_cndmask_b32_e32 v65, v65, v47, vcc
	s_cselect_b64 vcc, -1, 0
	s_cmp_eq_u32 s50, 1
	v_cndmask_b32_e32 v65, v65, v46, vcc
	s_cselect_b64 vcc, -1, 0
	s_cmp_eq_u32 s50, 2
	v_cndmask_b32_e32 v50, v50, v53, vcc
	s_cselect_b64 vcc, -1, 0
	s_cmp_eq_u32 s50, 3
	v_cndmask_b32_e32 v50, v50, v52, vcc
	s_cselect_b64 vcc, -1, 0
	s_cmp_eq_u32 s50, 4
	v_cndmask_b32_e32 v50, v50, v51, vcc
	s_cselect_b64 vcc, -1, 0
	s_cmp_eq_u32 s50, 5
	v_cndmask_b32_e32 v48, v50, v48, vcc
	s_cselect_b64 vcc, -1, 0
	s_cmp_eq_u32 s50, 6
	v_cndmask_b32_e32 v48, v48, v49, vcc
	s_cselect_b64 vcc, -1, 0
	v_cndmask_b32_e32 v47, v48, v47, vcc
	v_cndmask_b32_e64 v48, v42, v38, s[48:49]
	v_fmac_f32_e32 v48, 0, v56
	v_cndmask_b32_e64 v49, v43, v39, s[48:49]
	v_fmac_f32_e32 v49, v57, v48
	v_cndmask_b32_e64 v48, v44, v40, s[48:49]
	v_mul_f32_e32 v60, v56, v57
	v_fmac_f32_e32 v48, v61, v49
	v_cndmask_b32_e64 v49, v45, v41, s[48:49]
	v_mul_f32_e32 v60, v61, v60
	v_fmac_f32_e32 v49, v62, v48
	v_cndmask_b32_e64 v41, v41, v45, s[48:49]
	v_mul_f32_e32 v60, v62, v60
	s_cmp_eq_u32 s50, 7
	v_fmac_f32_e32 v41, v63, v49
	v_cndmask_b32_e64 v40, v40, v44, s[48:49]
	v_mul_f32_e32 v60, v63, v60
	s_cselect_b64 vcc, -1, 0
	v_fmac_f32_e32 v40, v64, v41
	v_cndmask_b32_e64 v39, v39, v43, s[48:49]
	v_mov_b32_e32 v55, s67
	v_or_b32_e32 v54, s66, v98
	v_mul_f32_e32 v60, v64, v60
	v_cndmask_b32_e32 v46, v47, v46, vcc
	v_fmac_f32_e32 v39, v65, v40
	v_cndmask_b32_e64 v42, v38, v42, s[48:49]
	v_mul_f32_e32 v60, v65, v60
	v_fmac_f32_e32 v42, v46, v39
	v_lshlrev_b64 v[38:39], 2, v[54:55]
	v_mul_f32_e32 v47, v46, v60
	v_lshl_add_u64 v[40:41], s[44:45], 0, v[38:39]
	v_lshl_add_u64 v[38:39], s[42:43], 0, v[38:39]
	global_store_dword v[38:39], v47, off
	global_store_dword v[40:41], v42, off
; __device__ __forceinline__ float sigm(float x) { return __builtin_amdgcn_rcpf(1.f + __expf(-x)); }
; #define MFMA16(a, b, c) __builtin_amdgcn_mfma_f32_16x16x32_bf16((a), (b), (c), 0, 0, 0)
; template <bool PASS2> ...
;     ...
;                 for (int ks = 0; ks < 2; ++ks) {
; #pragma unroll
;                     for (int tb = 0; tb < 2; ++tb) { ga[tb] = MFMA16(af[tb][ks], wfa[cb][ks], ga[tb]); gx[tb] = MFMA16(af[tb][ks], wfx[cb][ks], gx[tb]); } }
;                 const float ba = pba[cb], bx = pbx[cb], sp = log1pf(__expf(-plm[cb]));
; #pragma unroll
;                 for (int tb = 0; tb < 2; ++tb)
; #pragma unroll
;                     for (int q = 0; q < 4; ++q) { const float xv = xl[(tb * 16 + fq * 4 + q) * 68 + cb * 16 + fr];
;                         const float r = sigm(ga[tb][q] + ba), ig = sigm(gx[tb][q] + bx), la = -8.f * r * sp;
;                         const float aa = __expf(la), om = (1.f - aa) * (1.f + aa), bb = __builtin_amdgcn_sqrtf(om) * (ig * xv);
.LBB0_651:
	s_or_b64 exec, exec, s[4:5]
	s_waitcnt lgkmcnt(0)
	v_mfma_f32_16x16x32_bf16 v[38:41], v[2:5], v[30:33], 0
	s_mov_b64 s[4:5], -1
	v_mfma_f32_16x16x32_bf16 v[42:45], v[2:5], v[34:37], 0
	v_mfma_f32_16x16x32_bf16 v[30:33], v[14:17], v[30:33], 0
	v_mfma_f32_16x16x32_bf16 v[46:49], v[14:17], v[34:37], 0
	v_mfma_f32_16x16x32_bf16 v[38:41], v[6:9], v[22:25], v[38:41]
	v_mfma_f32_16x16x32_bf16 v[34:37], v[6:9], v[26:29], v[42:45]
	v_mfma_f32_16x16x32_bf16 v[30:33], v[18:21], v[22:25], v[30:33]
	v_mfma_f32_16x16x32_bf16 v[22:25], v[18:21], v[26:29], v[46:49]
	v_mul_f32_e32 v26, 0xbfb8aa3b, v108
	v_exp_f32_e32 v28, v26
	s_nop 3
	v_add_f32_e32 v35, v0, v35
	v_mul_f32_e32 v35, 0xbfb8aa3b, v35
	v_exp_f32_e32 v35, v35
	v_add_f32_e32 v29, 1.0, v28
	v_add_f32_e32 v26, -1.0, v29
	v_sub_f32_e32 v27, v26, v29
	v_add_f32_e32 v27, 1.0, v27
	v_sub_f32_e32 v26, v28, v26
	v_add_f32_e32 v42, v26, v27
	v_frexp_mant_f32_e32 v26, v29
	v_cmp_gt_f32_e32 vcc, s70, v26
	v_cvt_f64_f32_e32 v[26:27], v29
	v_frexp_exp_i32_f64_e32 v26, v[26:27]
	v_subbrev_co_u32_e32 v26, vcc, 0, v26, vcc
	v_sub_u32_e32 v27, 0, v26
	v_ldexp_f32 v29, v29, v27
	v_ldexp_f32 v27, v42, v27
	v_add_f32_e32 v42, -1.0, v29
	v_add_f32_e32 v43, 1.0, v42
	v_sub_f32_e32 v43, v29, v43
	v_add_f32_e32 v43, v27, v43
	v_add_f32_e32 v44, v42, v43
	v_sub_f32_e32 v42, v44, v42
	v_sub_f32_e32 v42, v43, v42
	v_add_f32_e32 v43, 1.0, v29
	v_add_f32_e32 v45, -1.0, v43
	v_sub_f32_e32 v29, v29, v45
	v_add_f32_e32 v27, v27, v29
	v_add_f32_e32 v29, v43, v27
	v_sub_f32_e32 v43, v29, v43
	v_sub_f32_e32 v27, v27, v43
	v_rcp_f32_e32 v43, v29
	v_cvt_f32_i32_e32 v26, v26
	v_cmp_neq_f32_e32 vcc, s12, v28
	v_add_f32_e32 v35, 1.0, v35
	v_mul_f32_e32 v45, v44, v43
	v_mul_f32_e32 v46, v29, v45
	v_fma_f32 v47, v45, v29, -v46
	v_fmac_f32_e32 v47, v45, v27
	v_add_f32_e32 v48, v46, v47
	v_sub_f32_e32 v49, v44, v48
	v_sub_f32_e32 v44, v44, v49
	v_sub_f32_e32 v46, v48, v46
	v_sub_f32_e32 v44, v44, v48
	v_add_f32_e32 v42, v42, v44
	v_sub_f32_e32 v44, v46, v47
	v_add_f32_e32 v42, v44, v42
	v_add_f32_e32 v44, v49, v42
	v_mul_f32_e32 v46, v43, v44
	v_mul_f32_e32 v47, v29, v46
	v_fma_f32 v29, v46, v29, -v47
	v_fmac_f32_e32 v29, v46, v27
	v_sub_f32_e32 v27, v49, v44
	v_add_f32_e32 v27, v42, v27
	v_add_f32_e32 v42, v47, v29
	v_sub_f32_e32 v48, v44, v42
	v_sub_f32_e32 v44, v44, v48
	v_sub_f32_e32 v47, v42, v47
	v_sub_f32_e32 v42, v44, v42
	v_add_f32_e32 v27, v27, v42
	v_sub_f32_e32 v29, v47, v29
	v_add_f32_e32 v27, v29, v27
	v_add_f32_e32 v29, v45, v46
	v_add_f32_e32 v27, v48, v27
	v_sub_f32_e32 v42, v29, v45
	v_mul_f32_e32 v27, v43, v27
	v_sub_f32_e32 v42, v46, v42
	v_add_f32_e32 v27, v42, v27
	v_mul_f32_e32 v45, 0x3f317218, v26
	v_add_f32_e32 v42, v29, v27
	v_fma_f32 v46, v26, s71, -v45
	v_mul_f32_e32 v43, v42, v42
	v_fmac_f32_e32 v46, 0xb102e308, v26
	v_sub_f32_e32 v26, v42, v29
	v_fmamk_f32 v44, v43, 0x3e9b6dac, v198
	v_sub_f32_e32 v26, v27, v26
	v_add_f32_e32 v27, v45, v46
	v_fmaak_f32 v44, v43, v44, 0x3f2aaada
	v_sub_f32_e32 v29, v27, v45
	v_ldexp_f32 v45, v42, 1
	v_mul_f32_e32 v42, v42, v43
	v_mul_f32_e32 v42, v42, v44
	v_add_f32_e32 v43, v45, v42
	v_sub_f32_e32 v44, v43, v45
	v_ldexp_f32 v26, v26, 1
	v_sub_f32_e32 v42, v42, v44
	v_add_f32_e32 v26, v26, v42
	v_add_f32_e32 v42, v43, v26
	v_sub_f32_e32 v43, v42, v43
	v_sub_f32_e32 v26, v26, v43
	v_add_f32_e32 v43, v27, v42
	v_sub_f32_e32 v44, v43, v27
	v_sub_f32_e32 v45, v43, v44
	v_sub_f32_e32 v29, v46, v29
	v_sub_f32_e32 v27, v27, v45
	v_sub_f32_e32 v42, v42, v44
	v_add_f32_e32 v27, v42, v27
	v_add_f32_e32 v42, v29, v26
	v_sub_f32_e32 v44, v42, v29
	v_sub_f32_e32 v45, v42, v44
	v_sub_f32_e32 v29, v29, v45
	v_sub_f32_e32 v26, v26, v44
	v_add_f32_e32 v27, v42, v27
	v_add_f32_e32 v26, v26, v29
	v_add_f32_e32 v29, v43, v27
	v_sub_f32_e32 v42, v29, v43
	v_sub_f32_e32 v27, v27, v42
	v_add_f32_e32 v26, v26, v27
	v_add_f32_e32 v26, v29, v26
	v_cndmask_b32_e32 v26, v203, v26, vcc
	v_cmp_ngt_f32_e32 vcc, -1.0, v28
	v_add_f32_e32 v29, v0, v34
	v_mul_f32_e32 v29, 0xbfb8aa3b, v29
	v_cndmask_b32_e32 v26, v204, v26, vcc
	v_cmp_neq_f32_e32 vcc, -1.0, v28
	v_exp_f32_e32 v29, v29
	v_rcp_f32_e32 v35, v35
	v_cndmask_b32_e32 v26, v205, v26, vcc
	v_cmp_lt_f32_e64 vcc, |v28|, s13
	v_add_f32_e32 v29, 1.0, v29
	v_rcp_f32_e32 v29, v29
	v_cndmask_b32_e32 v27, v26, v28, vcc
	v_add_f32_e32 v28, v107, v38
	v_mul_f32_e32 v28, 0xbfb8aa3b, v28
	v_exp_f32_e32 v28, v28
	ds_read_b32 v26, v106 offset:192
	v_add_f32_e32 v36, v0, v36
	v_mul_f32_e32 v36, 0xbfb8aa3b, v36
	v_add_f32_e32 v28, 1.0, v28
	v_rcp_f32_e32 v28, v28
	s_waitcnt lgkmcnt(0)
	v_mul_f32_e32 v26, v26, v29
	v_exp_f32_e32 v36, v36
	v_add_f32_e32 v30, v107, v30
	v_mul_f32_e32 v28, 0xc1000000, v28
	v_mul_f32_e32 v28, v27, v28
	v_mul_f32_e32 v34, 0x3fb8aa3b, v28
	v_exp_f32_e32 v34, v34
	v_add_f32_e32 v36, 1.0, v36
	v_rcp_f32_e32 v36, v36
	v_add_f32_e32 v37, v0, v37
	v_sub_f32_e32 v38, 1.0, v34
	v_add_f32_e32 v34, 1.0, v34
	v_mul_f32_e32 v34, v38, v34
	v_sqrt_f32_e32 v34, v34
	v_mul_f32_e32 v30, 0xbfb8aa3b, v30
	v_mul_f32_e32 v37, 0xbfb8aa3b, v37
	v_exp_f32_e32 v30, v30
	v_mul_f32_e32 v26, v26, v34
	v_add_f32_e32 v34, v107, v39
	v_mul_f32_e32 v34, 0xbfb8aa3b, v34
	v_exp_f32_e32 v34, v34
	v_cvt_pk_bf16_f32 v28, v28, v26
	ds_read_b32 v29, v106 offset:464
	global_store_dword v[104:105], v28, off offset:192
	v_add_f32_e32 v34, 1.0, v34
	v_rcp_f32_e32 v34, v34
	v_exp_f32_e32 v37, v37
	s_waitcnt lgkmcnt(0)
; __device__ __forceinline__ unsigned cvt_pk_bf16(float lo, float hi) { unsigned r; asm volatile("v_cvt_pk_bf16_f32 %0, %1, %2" : "=v"(r) : "v"(lo), "v"(hi)); return r; }
; __device__ __forceinline__ float bflo(unsigned w) { return __uint_as_float(w << 16); }
; __device__ __forceinline__ float bfhi(unsigned w) { return __uint_as_float(w & 0xffff0000u); }
; __device__ __forceinline__ float sigm(float x) { return __builtin_amdgcn_rcpf(1.f + __expf(-x)); }
; template <bool PASS2> ...
;     ...
;                     for (int q = 0; q < 4; ++q) { const float xv = xl[(tb * 16 + fq * 4 + q) * 68 + cb * 16 + fr];
;                         const float r = sigm(ga[tb][q] + ba), ig = sigm(gx[tb][q] + bx), la = -8.f * r * sp;
;                         const float aa = __expf(la), om = (1.f - aa) * (1.f + aa), bb = __builtin_amdgcn_sqrtf(om) * (ig * xv);
;                         const unsigned pk = cvt_pk_bf16(la, bb);
;                         labd[(size_t)(tb * 16 + q) * 256 + cb * 16] = pk;
;                         av[tb][q] = __expf(bflo(pk)); bv[tb][q] = bfhi(pk); }
	v_mul_f32_e32 v29, v35, v29
	v_add_f32_e32 v30, 1.0, v30
	v_mul_f32_e32 v34, 0xc1000000, v34
	v_mul_f32_e32 v34, v27, v34
	v_mul_f32_e32 v38, 0x3fb8aa3b, v34
	v_exp_f32_e32 v38, v38
	v_add_f32_e32 v37, 1.0, v37
	v_rcp_f32_e32 v30, v30
	v_add_f32_e32 v31, v107, v31
	v_sub_f32_e32 v39, 1.0, v38
	v_add_f32_e32 v38, 1.0, v38
	v_mul_f32_e32 v38, v39, v38
	v_sqrt_f32_e32 v38, v38
	v_rcp_f32_e32 v37, v37
	v_mul_f32_e32 v31, 0xbfb8aa3b, v31
	v_add_f32_e32 v22, v0, v22
	v_mul_f32_e32 v29, v29, v38
	v_add_f32_e32 v38, v107, v40
	v_mul_f32_e32 v38, 0xbfb8aa3b, v38
	v_exp_f32_e32 v38, v38
	v_cvt_pk_bf16_f32 v34, v34, v29
	ds_read_b32 v35, v106 offset:736
	global_store_dword v[104:105], v34, off offset:1216
	v_add_f32_e32 v38, 1.0, v38
	v_rcp_f32_e32 v38, v38
	v_exp_f32_e32 v31, v31
	s_waitcnt lgkmcnt(0)
	v_mul_f32_e32 v35, v36, v35
	v_mul_f32_e32 v22, 0xbfb8aa3b, v22
	v_mul_f32_e32 v38, 0xc1000000, v38
	v_mul_f32_e32 v38, v27, v38
	v_mul_f32_e32 v39, 0x3fb8aa3b, v38
	v_exp_f32_e32 v39, v39
	v_exp_f32_e32 v22, v22
	v_mul_f32_e32 v30, 0xc1000000, v30
	v_mul_f32_e32 v30, v27, v30
	v_sub_f32_e32 v40, 1.0, v39
	v_add_f32_e32 v39, 1.0, v39
	v_mul_f32_e32 v39, v40, v39
	v_sqrt_f32_e32 v39, v39
	v_add_f32_e32 v31, 1.0, v31
	v_rcp_f32_e32 v31, v31
	v_add_f32_e32 v22, 1.0, v22
	v_mul_f32_e32 v35, v35, v39
	v_add_f32_e32 v39, v107, v41
	v_mul_f32_e32 v39, 0xbfb8aa3b, v39
	v_exp_f32_e32 v39, v39
	v_cvt_pk_bf16_f32 v36, v38, v35
	ds_read_b32 v38, v106 offset:1008
	global_store_dword v[104:105], v36, off offset:2240
	v_add_f32_e32 v39, 1.0, v39
	v_rcp_f32_e32 v39, v39
	v_rcp_f32_e32 v22, v22
	s_waitcnt lgkmcnt(0)
	v_mul_f32_e32 v37, v37, v38
	v_mul_f32_e32 v31, 0xc1000000, v31
	v_mul_f32_e32 v39, 0xc1000000, v39
	v_mul_f32_e32 v39, v27, v39
	v_mul_f32_e32 v40, 0x3fb8aa3b, v39
	v_exp_f32_e32 v40, v40
	v_add_f32_e32 v23, v0, v23
	v_mul_f32_e32 v31, v27, v31
	v_mul_f32_e32 v23, 0xbfb8aa3b, v23
	v_sub_f32_e32 v41, 1.0, v40
	v_add_f32_e32 v40, 1.0, v40
	v_mul_f32_e32 v40, v41, v40
	v_sqrt_f32_e32 v40, v40
	v_exp_f32_e32 v23, v23
	v_add_f32_e32 v24, v0, v24
	v_mul_f32_e32 v24, 0xbfb8aa3b, v24
	v_mul_f32_e32 v37, v40, v37
	v_mul_f32_e32 v40, 0x3fb8aa3b, v30
	v_exp_f32_e32 v40, v40
	v_cvt_pk_bf16_f32 v38, v39, v37
	ds_read_b32 v39, v106 offset:4544
	global_store_dword v[104:105], v38, off offset:3264
	v_sub_f32_e32 v41, 1.0, v40
	v_add_f32_e32 v40, 1.0, v40
	v_mul_f32_e32 v40, v41, v40
	v_sqrt_f32_e32 v40, v40
	s_waitcnt lgkmcnt(0)
	v_mul_f32_e32 v22, v22, v39
	v_mul_f32_e32 v39, 0x3fb8aa3b, v31
	v_exp_f32_e32 v39, v39
	v_mul_f32_e32 v22, v40, v22
	v_cvt_pk_bf16_f32 v22, v30, v22
	ds_read_b32 v30, v106 offset:4816
	v_add_f32_e32 v23, 1.0, v23
	v_sub_f32_e32 v40, 1.0, v39
	v_add_f32_e32 v39, 1.0, v39
	v_rcp_f32_e32 v23, v23
	v_mul_f32_e32 v39, v40, v39
	v_sqrt_f32_e32 v39, v39
	global_store_dword v[74:75], v22, off offset:192
	s_waitcnt lgkmcnt(0)
	v_mul_f32_e32 v23, v23, v30
	v_exp_f32_e32 v24, v24
	v_mul_f32_e32 v23, v39, v23
	v_cvt_pk_bf16_f32 v23, v31, v23
	v_add_f32_e32 v31, v107, v32
	v_mul_f32_e32 v31, 0xbfb8aa3b, v31
	v_exp_f32_e32 v31, v31
	ds_read_b32 v30, v106 offset:5088
	v_add_f32_e32 v24, 1.0, v24
	v_rcp_f32_e32 v24, v24
	v_add_f32_e32 v31, 1.0, v31
	v_rcp_f32_e32 v31, v31
	global_store_dword v[74:75], v23, off offset:1216
	s_waitcnt lgkmcnt(0)
	v_mul_f32_e32 v24, v24, v30
	v_add_f32_e32 v0, v0, v25
	v_mul_f32_e32 v31, 0xc1000000, v31
	v_mul_f32_e32 v31, v27, v31
	v_mul_f32_e32 v32, 0x3fb8aa3b, v31
	v_exp_f32_e32 v32, v32
	v_mul_f32_e32 v0, 0xbfb8aa3b, v0
	v_exp_f32_e32 v0, v0
	v_lshlrev_b32_e32 v26, 16, v28
	v_sub_f32_e32 v39, 1.0, v32
	v_add_f32_e32 v32, 1.0, v32
	v_mul_f32_e32 v32, v39, v32
	v_sqrt_f32_e32 v32, v32
	v_add_f32_e32 v0, 1.0, v0
	v_lshlrev_b32_e32 v29, 16, v34
	v_lshlrev_b32_e32 v35, 16, v36
	v_mul_f32_e32 v24, v32, v24
	v_cvt_pk_bf16_f32 v24, v31, v24
	v_add_f32_e32 v31, v107, v33
	v_mul_f32_e32 v31, 0xbfb8aa3b, v31
	v_exp_f32_e32 v31, v31
	ds_read_b32 v30, v106 offset:5360
	v_rcp_f32_e32 v0, v0
	v_mul_f32_e32 v26, 0x3fb8aa3b, v26
	v_add_f32_e32 v31, 1.0, v31
	v_rcp_f32_e32 v31, v31
	v_mul_f32_e32 v29, 0x3fb8aa3b, v29
	v_mul_f32_e32 v35, 0x3fb8aa3b, v35
	v_exp_f32_e32 v26, v26
	v_mul_f32_e32 v25, 0xc1000000, v31
	v_mul_f32_e32 v25, v27, v25
	v_mul_f32_e32 v27, 0x3fb8aa3b, v25
	v_exp_f32_e32 v27, v27
	v_exp_f32_e32 v29, v29
	v_exp_f32_e32 v35, v35
	s_waitcnt lgkmcnt(0)
	v_mul_f32_e32 v0, v0, v30
	v_sub_f32_e32 v31, 1.0, v27
	v_add_f32_e32 v27, 1.0, v27
	v_mul_f32_e32 v27, v31, v27
	v_sqrt_f32_e32 v27, v27
	v_and_b32_e32 v28, 0xffff0000, v28
	v_and_b32_e32 v34, 0xffff0000, v34
	v_and_b32_e32 v36, 0xffff0000, v36
	v_and_b32_e32 v37, 0xffff0000, v38
	v_mul_f32_e32 v0, v27, v0
	s_and_b64 vcc, exec, s[38:39]
	global_store_dword v[74:75], v24, off offset:2240
	v_cvt_pk_bf16_f32 v0, v25, v0
	global_store_dword v[74:75], v0, off offset:3264
	s_cbranch_vccnz .LBB0_653
	v_fma_f32 v25, v35, v37, v36
	v_fma_f32 v25, v29, v25, v34
	v_fma_f32 v25, v26, v25, v28
	s_mov_b64 s[4:5], 0

; template <bool PASS2> ...
;     ...
;             for (int tb = 0; tb < 2; ++tb) {
;                 Ap[tb] = (av[tb][0] * av[tb][1]) * (av[tb][2] * av[tb][3]);
;                 Bp[tb] = d == 0 ? ((bv[tb][0] * av[tb][1] + bv[tb][1]) * av[tb][2] + bv[tb][2]) * av[tb][3] + bv[tb][3]
;                                 : ((bv[tb][3] * av[tb][2] + bv[tb][2]) * av[tb][1] + bv[tb][1]) * av[tb][0] + bv[tb][0];
;             }
;             float PA[8], PB[8];
; #pragma unroll
;             for (int e = 0; e < 8; ++e) { PA[e] = __shfl(Ap[e >> 2], (e & 3) * 16 + fr); PB[e] = __shfl(Bp[e >> 2], (e & 3) * 16 + fr); }
;             const size_t si = ((size_t)(b * NCH + c) * 2 + d) * 256 + chn;
;             if (!PASS2) {
;                 float At = 1.f, Bt = 0.f;
; #pragma unroll
;                 for (int e2 = 0; e2 < 8; ++e2) { const int e = d == 0 ? e2 : 7 - e2; Bt = PA[e] * Bt + PB[e]; At *= PA[e]; }
;                 if (fq == 0) { LRA[si] = At; LRB[si] = Bt; }
.LBB0_659:
	v_mul_f32_e32 v22, v28, v22
	v_mul_f32_e32 v0, v23, v0
	v_mul_f32_e32 v38, v22, v0
	v_mul_f32_e32 v0, v26, v29
	v_mul_f32_e32 v22, v35, v27
	v_mul_f32_e32 v24, v0, v22
	ds_bpermute_b32 v33, v76, v24
	ds_bpermute_b32 v0, v76, v25
	ds_bpermute_b32 v36, v59, v24
	ds_bpermute_b32 v22, v59, v25
	ds_bpermute_b32 v35, v58, v24
	ds_bpermute_b32 v23, v58, v25
	ds_bpermute_b32 v34, v77, v24
	ds_bpermute_b32 v24, v77, v25
	ds_bpermute_b32 v31, v76, v38
	ds_bpermute_b32 v28, v76, v37
	ds_bpermute_b32 v32, v59, v38
	ds_bpermute_b32 v27, v59, v37
	ds_bpermute_b32 v30, v58, v38
	ds_bpermute_b32 v26, v58, v37
	ds_bpermute_b32 v29, v77, v38
	ds_bpermute_b32 v25, v77, v37
	s_and_saveexec_b64 s[4:5], s[36:37]
	s_cbranch_execz .LBB0_619
	s_cmp_eq_u32 s64, 1
	s_cselect_b64 vcc, -1, 0
	s_cmp_eq_u32 s64, 2
	s_waitcnt lgkmcnt(0)
	v_cndmask_b32_e32 v37, v33, v36, vcc
	s_cselect_b64 vcc, -1, 0
	s_cmp_eq_u32 s64, 3
	v_cndmask_b32_e32 v37, v37, v35, vcc
	s_cselect_b64 vcc, -1, 0
	s_cmp_eq_u32 s64, 4
	v_cndmask_b32_e32 v37, v37, v34, vcc
	s_cselect_b64 vcc, -1, 0
	s_cmp_eq_u32 s64, 5
	v_cndmask_b32_e32 v37, v37, v31, vcc
	s_cselect_b64 vcc, -1, 0
	s_cmp_eq_u32 s64, 6
	v_cndmask_b32_e32 v37, v37, v32, vcc
	s_cselect_b64 vcc, -1, 0
	s_cmp_eq_u32 s64, 7
	v_cndmask_b32_e32 v37, v37, v30, vcc
	s_cselect_b64 vcc, -1, 0
	s_cmp_eq_u32 s62, 1
	v_cndmask_b32_e32 v37, v37, v29, vcc
	s_cselect_b64 vcc, -1, 0
	s_cmp_eq_u32 s62, 2
	v_cndmask_b32_e32 v40, v33, v36, vcc
	s_cselect_b64 vcc, -1, 0
	s_cmp_eq_u32 s62, 3
	v_cndmask_b32_e32 v40, v40, v35, vcc
	s_cselect_b64 vcc, -1, 0
	s_cmp_eq_u32 s62, 4
	v_cndmask_b32_e32 v40, v40, v34, vcc
	s_cselect_b64 vcc, -1, 0
	s_cmp_eq_u32 s62, 5
	v_cndmask_b32_e32 v40, v40, v31, vcc
	s_cselect_b64 vcc, -1, 0
	s_cmp_eq_u32 s62, 6
	v_cndmask_b32_e32 v40, v40, v32, vcc
	s_cselect_b64 vcc, -1, 0
	s_cmp_eq_u32 s62, 7
	v_cndmask_b32_e32 v40, v40, v30, vcc
	s_cselect_b64 vcc, -1, 0
	s_cmp_eq_u32 s60, 1
	v_cndmask_b32_e32 v40, v40, v29, vcc
	s_cselect_b64 vcc, -1, 0
	s_cmp_eq_u32 s60, 2
	v_cndmask_b32_e32 v42, v33, v36, vcc
	s_cselect_b64 vcc, -1, 0
	s_cmp_eq_u32 s60, 3
	v_cndmask_b32_e32 v42, v42, v35, vcc
	s_cselect_b64 vcc, -1, 0
	s_cmp_eq_u32 s60, 4
	v_cndmask_b32_e32 v42, v42, v34, vcc
	s_cselect_b64 vcc, -1, 0
	s_cmp_eq_u32 s60, 5
	v_cndmask_b32_e32 v42, v42, v31, vcc
	s_cselect_b64 vcc, -1, 0
	s_cmp_eq_u32 s60, 6
	v_cndmask_b32_e32 v42, v42, v32, vcc
	s_cselect_b64 vcc, -1, 0
	s_cmp_eq_u32 s60, 7
	v_cndmask_b32_e32 v42, v42, v30, vcc
	s_cselect_b64 vcc, -1, 0
	s_cmp_eq_u32 s58, 1
	v_cndmask_b32_e32 v42, v42, v29, vcc
	s_cselect_b64 vcc, -1, 0
	s_cmp_eq_u32 s58, 2
	v_cndmask_b32_e32 v43, v33, v36, vcc
	s_cselect_b64 vcc, -1, 0
	s_cmp_eq_u32 s58, 3
	v_cndmask_b32_e32 v43, v43, v35, vcc
	s_cselect_b64 vcc, -1, 0
	s_cmp_eq_u32 s58, 4
	v_cndmask_b32_e32 v43, v43, v34, vcc
	s_cselect_b64 vcc, -1, 0
	s_cmp_eq_u32 s58, 5
	v_cndmask_b32_e32 v43, v43, v31, vcc
	s_cselect_b64 vcc, -1, 0
	s_cmp_eq_u32 s58, 6
	v_cndmask_b32_e32 v43, v43, v32, vcc
	s_cselect_b64 vcc, -1, 0
	s_cmp_eq_u32 s58, 7
	v_cndmask_b32_e32 v43, v43, v30, vcc
	s_cselect_b64 vcc, -1, 0
	s_cmp_eq_u32 s56, 1
	v_cndmask_b32_e32 v43, v43, v29, vcc
	s_cselect_b64 vcc, -1, 0
	s_cmp_eq_u32 s56, 2
	v_cndmask_b32_e32 v44, v33, v36, vcc
	s_cselect_b64 vcc, -1, 0
	s_cmp_eq_u32 s56, 3
	v_cndmask_b32_e32 v44, v44, v35, vcc
	s_cselect_b64 vcc, -1, 0
	s_cmp_eq_u32 s56, 4
	v_cndmask_b32_e32 v44, v44, v34, vcc
	s_cselect_b64 vcc, -1, 0
	s_cmp_eq_u32 s56, 5
	v_cndmask_b32_e32 v44, v44, v31, vcc
	s_cselect_b64 vcc, -1, 0
	s_cmp_eq_u32 s56, 6
	v_cndmask_b32_e32 v44, v44, v32, vcc
	s_cselect_b64 vcc, -1, 0
	s_cmp_eq_u32 s56, 7
	v_cndmask_b32_e32 v44, v44, v30, vcc
	s_cselect_b64 vcc, -1, 0
	s_cmp_eq_u32 s54, 1
	v_cndmask_b32_e32 v44, v44, v29, vcc
	s_cselect_b64 vcc, -1, 0
	s_cmp_eq_u32 s54, 2
	v_cndmask_b32_e32 v45, v33, v36, vcc
	s_cselect_b64 vcc, -1, 0
	s_cmp_eq_u32 s54, 3
	v_cndmask_b32_e32 v45, v45, v35, vcc
	s_cselect_b64 vcc, -1, 0
	s_cmp_eq_u32 s54, 4
	v_cndmask_b32_e32 v45, v45, v34, vcc
	s_cselect_b64 vcc, -1, 0
	s_cmp_eq_u32 s54, 5
	v_cndmask_b32_e32 v45, v45, v31, vcc
	s_cselect_b64 vcc, -1, 0
	s_cmp_eq_u32 s54, 6
	v_cndmask_b32_e32 v45, v45, v32, vcc
	s_cselect_b64 vcc, -1, 0
	s_cmp_eq_u32 s54, 7
	v_cndmask_b32_e32 v45, v45, v30, vcc
	s_cselect_b64 vcc, -1, 0
	s_cmp_eq_u32 s52, 1
	v_cndmask_b32_e32 v45, v45, v29, vcc
	s_cselect_b64 vcc, -1, 0
	s_cmp_eq_u32 s52, 2
	v_cndmask_b32_e32 v46, v33, v36, vcc
	s_cselect_b64 vcc, -1, 0
	s_cmp_eq_u32 s52, 3
	v_cndmask_b32_e32 v46, v46, v35, vcc
	s_cselect_b64 vcc, -1, 0
	s_cmp_eq_u32 s52, 4
	v_cndmask_b32_e32 v46, v46, v34, vcc
	s_cselect_b64 vcc, -1, 0
	s_cmp_eq_u32 s52, 5
	v_cndmask_b32_e32 v46, v46, v31, vcc
	s_cselect_b64 vcc, -1, 0
	s_cmp_eq_u32 s52, 6
	v_cndmask_b32_e32 v46, v46, v32, vcc
	s_cselect_b64 vcc, -1, 0
	s_cmp_eq_u32 s52, 7
	v_cndmask_b32_e32 v46, v46, v30, vcc
	s_cselect_b64 vcc, -1, 0
	s_cmp_eq_u32 s50, 1
	v_cndmask_b32_e32 v46, v46, v29, vcc
	s_cselect_b64 vcc, -1, 0
	s_cmp_eq_u32 s50, 2
	v_cndmask_b32_e32 v33, v33, v36, vcc
	s_cselect_b64 vcc, -1, 0
	s_cmp_eq_u32 s50, 3
	v_cndmask_b32_e32 v33, v33, v35, vcc
	s_cselect_b64 vcc, -1, 0
	s_cmp_eq_u32 s50, 4
	v_cndmask_b32_e32 v33, v33, v34, vcc
	s_cselect_b64 vcc, -1, 0
	s_cmp_eq_u32 s50, 5
	v_cndmask_b32_e32 v31, v33, v31, vcc
	s_cselect_b64 vcc, -1, 0
	s_cmp_eq_u32 s50, 6
	v_cndmask_b32_e32 v31, v31, v32, vcc
	s_cselect_b64 vcc, -1, 0
	v_cndmask_b32_e32 v30, v31, v30, vcc
	v_cndmask_b32_e64 v31, v25, v0, s[48:49]
	v_fmac_f32_e32 v31, 0, v37
	v_cndmask_b32_e64 v32, v26, v22, s[48:49]
	v_fmac_f32_e32 v32, v40, v31
	v_cndmask_b32_e64 v31, v27, v23, s[48:49]
	v_mul_f32_e32 v41, v37, v40
	v_fmac_f32_e32 v31, v42, v32
	v_cndmask_b32_e64 v32, v28, v24, s[48:49]
	v_mul_f32_e32 v41, v42, v41
	v_fmac_f32_e32 v32, v43, v31
	v_cndmask_b32_e64 v24, v24, v28, s[48:49]
	v_mul_f32_e32 v41, v43, v41
	s_cmp_eq_u32 s50, 7
	v_fmac_f32_e32 v24, v44, v32
	v_cndmask_b32_e64 v23, v23, v27, s[48:49]
	v_mul_f32_e32 v41, v44, v41
	s_cselect_b64 vcc, -1, 0
	v_fmac_f32_e32 v23, v45, v24
	v_cndmask_b32_e64 v22, v22, v26, s[48:49]
	v_mov_b32_e32 v39, s67
	v_or_b32_e32 v38, s66, v100
	v_mul_f32_e32 v41, v45, v41
	v_cndmask_b32_e32 v29, v30, v29, vcc
	v_fmac_f32_e32 v22, v46, v23
	v_cndmask_b32_e64 v0, v0, v25, s[48:49]
	v_mul_f32_e32 v41, v46, v41
	v_fmac_f32_e32 v0, v29, v22
	v_lshlrev_b64 v[22:23], 2, v[38:39]
	v_mul_f32_e32 v30, v29, v41
	v_lshl_add_u64 v[24:25], s[44:45], 0, v[22:23]
	v_lshl_add_u64 v[22:23], s[42:43], 0, v[22:23]
	global_store_dword v[22:23], v30, off
	global_store_dword v[24:25], v0, off
	s_branch .LBB0_619

; #define LDX(tt) (((tt) >= 0 && (tt) < seqlen) ? bf1(xp[(size_t)(tt) * INP]) : 0.f)
; #define LDX(tt) (((tt) >= 0 && (tt) < seqlen) ? bf1(xp[(size_t)(tt) * INP]) : 0.f)
; template <bool PASS2> ...
;     ...
;     const int blk = t & 3, c = (t >> 2) % NCH, b = (t >> 2) / NCH;
;     const int seqlen = c < 8 ? 256 : 2048, t0 = c < 8 ? c * 32 : (c - 8) * 32, rbase = c < 8 ? ML + b * 256 : b * 2048;
;     bf16x8 af[2][2];
;     if (!PASS2) {
;         const int ch = blk * 64 + lane;
;         const float w0 = convw[(l * 4 + 0) * 256 + ch], w1 = convw[(l * 4 + 1) * 256 + ch], w2 = convw[(l * 4 + 2) * 256 + ch], w3 = convw[(l * 4 + 3) * 256 + ch], cb = convb[l * 256 + ch];
;         const bf16_t* xp = P + (size_t)rbase * INP + OFF_LRU + ch;
;     ...
;         float xs[35];
; #pragma unroll
;         for (int s = 0; s < 35; ++s) xs[s] = LDX(t0 + s - 2);
.LBB0_667:
	s_ashr_i32 s4, s23, 2
	s_mul_hi_i32 s1, s4, 0x38e38e39
	s_lshr_b32 s5, s1, 31
	s_ashr_i32 s1, s1, 4
	s_add_i32 s1, s1, s5
	s_mul_i32 s5, s1, 0x48
	s_sub_i32 s5, s4, s5
	s_lshl_b32 s7, s5, 5
	s_lshl_b32 s6, s1, 8
	s_add_i32 s14, s7, 0xffffff00
	s_add_i32 s15, s6, 0x4000
	s_lshl_b32 s1, s1, 11
	s_cmp_lt_i32 s5, 8
	s_movk_i32 s5, 0x800
	s_cselect_b32 s6, 0x100, s5
	s_cselect_b32 s38, s7, s14
	s_cselect_b32 s1, s15, s1
	s_lshl_b32 s5, s23, 6
	s_and_b32 s5, s5, 0xc0
	v_or_b32_e32 v9, s5, v95
	v_readlane_b32 s7, v254, 32
	v_readlane_b32 s48, v251, 24
	v_readlane_b32 s49, v251, 25
	s_waitcnt lgkmcnt(0)
	v_or_b32_e32 v0, s7, v9
	v_readlane_b32 s50, v251, 26
	v_readlane_b32 s51, v251, 27
	v_readlane_b32 s52, v251, 28
	v_readlane_b32 s53, v251, 29
	v_readlane_b32 s54, v251, 30
	v_readlane_b32 s55, v251, 31
	v_readlane_b32 s56, v251, 32
	v_readlane_b32 s57, v251, 33
	v_readlane_b32 s58, v251, 34
	v_readlane_b32 s59, v251, 35
	v_readlane_b32 s60, v251, 36
	v_readlane_b32 s61, v251, 37
	v_readlane_b32 s62, v251, 38
	v_readlane_b32 s63, v251, 39
	v_readlane_b32 s14, v254, 21
	s_mul_hi_i32 s7, s1, 0x2200
	v_lshl_add_u64 v[2:3], v[0:1], 2, s[62:63]
	v_readlane_b32 s48, v251, 40
	global_load_dword v7, v[2:3], off
	global_load_dword v6, v[2:3], off offset:1024
	global_load_dword v5, v[2:3], off offset:2048
	global_load_dword v4, v[2:3], off offset:3072
	v_or_b32_e32 v0, s14, v9
	v_readlane_b32 s49, v251, 41
	s_mul_i32 s14, s1, 0x2200
	s_add_u32 s18, s40, s14
	v_lshl_add_u64 v[2:3], v[0:1], 2, s[48:49]
	global_load_dword v8, v[2:3], off
	s_addc_u32 s19, s41, s7
	v_lshlrev_b32_e32 v0, 1, v9
	s_cmp_lt_i32 s38, 2
	v_lshl_add_u64 v[2:3], s[18:19], 0, v[0:1]
	s_cselect_b64 s[18:19], -1, 0
	s_cmp_le_i32 s38, s6
	s_cselect_b64 s[20:21], -1, 0
	s_cmp_gt_i32 s38, s6
	v_readlane_b32 s15, v254, 22
	s_cselect_b64 s[24:25], -1, 0
	s_mov_b64 s[14:15], 0x8eb8340
	s_or_b64 s[18:19], s[18:19], s[24:25]
	v_lshl_add_u64 v[2:3], v[2:3], 0, s[14:15]
	v_mov_b32_e32 v0, 0
	s_and_b64 vcc, exec, s[18:19]
	v_mov_b32_e32 v9, 0
	v_readlane_b32 s50, v251, 42
	v_readlane_b32 s51, v251, 43
	v_readlane_b32 s52, v251, 44
	v_readlane_b32 s53, v251, 45
	v_readlane_b32 s54, v251, 46
	v_readlane_b32 s55, v251, 47
	v_readlane_b32 s56, v251, 48
	v_readlane_b32 s57, v251, 49
	v_readlane_b32 s58, v251, 50
	v_readlane_b32 s59, v251, 51
	v_readlane_b32 s60, v251, 52
	v_readlane_b32 s61, v251, 53
	v_readlane_b32 s62, v251, 54
	v_readlane_b32 s63, v251, 55
	s_cbranch_vccnz .LBB0_669
	s_add_i32 s7, s38, -2
	v_mad_u64_u32 v[14:15], s[18:19], s7, v202, v[2:3]
	global_load_ushort v9, v[14:15], off
	s_nop 0
	s_nop 0

; template <bool PASS2> ...
;     ...
;         bf16x8 wfa[4][2], wfx[4][2]; float pba[4], pbx[4], plm[4], phin[4]; unsigned pkv[4][2][4];
;         unsigned* labd = LAB + ((size_t)d * MH + rbase + t0 + fq * 4) * 256 + blk * 64 + fr;
; #pragma unroll
;         for (int cb = 0; cb < 4; ++cb) {
;             const int chn = blk * 64 + cb * 16 + fr;
;             if (!PASS2) {
;                 const bf16_t* wa = WLRU + ((size_t)(((l * 2 + d) * 2 + 0) * 4 + blk) * 64 + cb * 16 + fr) * 64 + fq * 8;
; #pragma unroll
;                 for (int ks = 0; ks < 2; ++ks) { wfa[cb][ks] = asfrag(ld8(wa + ks * 32)); wfx[cb][ks] = asfrag(ld8(wa + 4 * 4096 + ks * 32)); }
;                 pba[cb] = b_a[(l * 2 + d) * 256 + chn]; pbx[cb] = b_x[(l * 2 + d) * 256 + chn]; plm[cb] = lam[(l * 2 + d) * 256 + chn];
;             } else {
;                 phin[cb] = LRH[((size_t)(b * NCH + c) * 2 + d) * 256 + chn];
; #pragma unroll
;                 for (int tb = 0; tb < 2; ++tb)
; #pragma unroll
;                     for (int q = 0; q < 4; ++q) pkv[cb][tb][q] = labd[(size_t)(tb * 16 + q) * 256 + cb * 16];
;             }
;         }
; #pragma unroll
;         for (int cb = 0; cb < 4; ++cb) {
;             const int chn = blk * 64 + cb * 16 + fr;
;             float av[2][4], bv[2][4], Ap[2], Bp[2];
;             if (!PASS2) {
;                 f32x4 ga[2], gx[2];
;                 ga[0] = ga[1] = gx[0] = gx[1] = (f32x4){0.f, 0.f, 0.f, 0.f};
; #pragma unroll
;                 for (int ks = 0; ks < 2; ++ks) {
; #pragma unroll
;                     for (int tb = 0; tb < 2; ++tb) { ga[tb] = MFMA16(af[tb][ks], wfa[cb][ks], ga[tb]); gx[tb] = MFMA16(af[tb][ks], wfx[cb][ks], gx[tb]); } }
;                 const float ba = pba[cb], bx = pbx[cb], sp = log1pf(__expf(-plm[cb]));
; #pragma unroll
;                 for (int tb = 0; tb < 2; ++tb)
; #pragma unroll
;                     for (int q = 0; q < 4; ++q) { const float xv = xl[(tb * 16 + fq * 4 + q) * 68 + cb * 16 + fr];
;                         const float r = sigm(ga[tb][q] + ba), ig = sigm(gx[tb][q] + bx), la = -8.f * r * sp;
;                         const float aa = __expf(la), om = (1.f - aa) * (1.f + aa), bb = __builtin_amdgcn_sqrtf(om) * (ig * xv);
;                         const unsigned pk = cvt_pk_bf16(la, bb);
;                         labd[(size_t)(tb * 16 + q) * 256 + cb * 16] = pk;
.LBB0_739:
	s_or_b32 s1, s4, s2
	s_waitcnt lgkmcnt(0)
	v_lshlrev_b32_e32 v0, 6, v94
	v_lshl_or_b32 v0, s1, 15, v0
	v_lshl_add_u64 v[26:27], v[0:1], 1, v[90:91]
	global_load_dwordx4 v[22:25], v[26:27], off
	global_load_dwordx4 v[66:69], v[26:27], off offset:64
	v_add_co_u32_e32 v122, vcc, s33, v26
	v_mov_b32_e32 v29, v1
	v_lshl_or_b32 v28, s1, 8, v94
	v_readlane_b32 s52, v251, 40
	v_addc_co_u32_e32 v123, vcc, 0, v27, vcc
	v_lshlrev_b64 v[28:29], 2, v[28:29]
	v_readlane_b32 s54, v251, 42
	v_readlane_b32 s55, v251, 43
	global_load_dwordx4 v[62:65], v[122:123], off
	v_readlane_b32 s58, v251, 46
	v_lshl_add_u64 v[124:125], s[54:55], 0, v[28:29]
	global_load_dword v126, v[124:125], off
	global_load_dwordx4 v[78:81], v[122:123], off offset:64
	v_readlane_b32 s59, v251, 47
	v_readlane_b32 s62, v251, 50
	v_readlane_b32 s63, v251, 51
	v_lshl_add_u64 v[74:75], s[58:59], 0, v[28:29]
	s_mov_b32 s1, 0x9000
	v_lshl_add_u64 v[76:77], s[62:63], 0, v[28:29]
	v_add_co_u32_e32 v28, vcc, s90, v26
	s_mul_i32 s88, s4, 0x4800
	s_nop 0
	v_addc_co_u32_e32 v29, vcc, 0, v27, vcc
	global_load_dwordx4 v[58:61], v[26:27], off offset:2048
	global_load_dwordx4 v[54:57], v[26:27], off offset:2112
	v_add_co_u32_e32 v26, vcc, s1, v26
	v_lshl_add_u64 v[30:31], v[102:103], 0, s[88:89]
	s_nop 0
	v_addc_co_u32_e32 v27, vcc, 0, v27, vcc
	v_lshlrev_b64 v[104:105], 10, v[30:31]
	global_load_dwordx4 v[46:49], v[28:29], off
	global_load_dwordx4 v[38:41], v[28:29], off offset:64
	global_load_dwordx4 v[50:53], v[26:27], off
	global_load_dwordx4 v[42:45], v[26:27], off offset:64
	v_lshl_add_u64 v[104:105], v[92:93], 0, v[104:105]
	s_xor_b64 s[50:51], s[48:49], -1
	s_mov_b64 s[20:21], -1
	v_readlane_b32 s53, v251, 41
	v_readlane_b32 s56, v251, 44
	v_readlane_b32 s57, v251, 45
	v_readlane_b32 s60, v251, 48
	v_readlane_b32 s61, v251, 49
	v_readlane_b32 s64, v251, 52
	v_readlane_b32 s65, v251, 53
	v_readlane_b32 s66, v251, 54
	v_readlane_b32 s67, v251, 55
	s_waitcnt vmcnt(0) lgkmcnt(0)
	v_mfma_f32_16x16x32_bf16 v[70:73], v[2:5], v[22:25], 0
	v_mfma_f32_16x16x32_bf16 v[82:85], v[14:17], v[22:25], 0
	global_load_dwordx4 v[30:33], v[28:29], off offset:2048
	global_load_dwordx4 v[22:25], v[28:29], off offset:2112
	global_load_dwordx4 v[34:37], v[26:27], off offset:2048
	s_nop 0
	global_load_dwordx4 v[26:29], v[26:27], off offset:2112
	s_nop 0
	global_load_dword v127, v[74:75], off
	global_load_dword v112, v[74:75], off offset:64
	global_load_dword v109, v[74:75], off offset:128
	global_load_dword v106, v[74:75], off offset:192
	global_load_dword v128, v[76:77], off
	global_load_dword v111, v[76:77], off offset:64
	global_load_dword v108, v[76:77], off offset:128
	global_load_dword v0, v[76:77], off offset:192
	v_mfma_f32_16x16x32_bf16 v[114:117], v[2:5], v[62:65], 0
	global_load_dword v113, v[124:125], off offset:64
	global_load_dword v110, v[124:125], off offset:128
	global_load_dword v107, v[124:125], off offset:192
	v_mfma_f32_16x16x32_bf16 v[118:121], v[14:17], v[62:65], 0
	v_mul_f32_e32 v62, 0xbfb8aa3b, v126
	v_exp_f32_e32 v124, v62
	v_mfma_f32_16x16x32_bf16 v[74:77], v[6:9], v[66:69], v[70:73]
	v_mfma_f32_16x16x32_bf16 v[70:73], v[18:21], v[66:69], v[82:85]
	global_load_dwordx4 v[66:69], v[122:123], off offset:2048
	global_load_dwordx4 v[62:65], v[122:123], off offset:2112
	s_waitcnt vmcnt(0)
	s_nop 3
	v_add_f32_e32 v74, v127, v74
	v_mfma_f32_16x16x32_bf16 v[82:85], v[6:9], v[78:81], v[114:117]
	v_mul_f32_e32 v74, 0xbfb8aa3b, v74
	v_exp_f32_e32 v74, v74
	v_add_f32_e32 v75, v127, v75
	v_add_f32_e32 v116, 1.0, v124
	v_add_f32_e32 v117, -1.0, v116
	v_frexp_mant_f32_e32 v122, v116
	v_cvt_f64_f32_e32 v[114:115], v116
	v_sub_f32_e32 v123, v117, v116
	v_frexp_exp_i32_f64_e32 v114, v[114:115]
	v_cmp_gt_f32_e32 vcc, s70, v122
	v_sub_f32_e32 v117, v124, v117
	v_add_f32_e32 v115, 1.0, v123
	v_subbrev_co_u32_e32 v114, vcc, 0, v114, vcc
	v_add_f32_e32 v115, v117, v115
	v_sub_u32_e32 v117, 0, v114
	v_ldexp_f32 v116, v116, v117
	v_ldexp_f32 v115, v115, v117
	v_add_f32_e32 v117, -1.0, v116
	v_add_f32_e32 v122, 1.0, v116
	v_add_f32_e32 v123, 1.0, v117
	v_add_f32_e32 v125, -1.0, v122
	v_sub_f32_e32 v123, v116, v123
	v_sub_f32_e32 v116, v116, v125
	v_add_f32_e32 v123, v115, v123
	v_add_f32_e32 v115, v115, v116
	v_add_f32_e32 v125, v122, v115
	v_rcp_f32_e32 v126, v125
	v_add_f32_e32 v116, v117, v123
	v_sub_f32_e32 v122, v125, v122
	v_sub_f32_e32 v117, v116, v117
	v_sub_f32_e32 v115, v115, v122
	v_mul_f32_e32 v122, v116, v126
	v_sub_f32_e32 v117, v123, v117
	v_mul_f32_e32 v123, v125, v122
	v_fma_f32 v129, v122, v125, -v123
	v_fmac_f32_e32 v129, v122, v115
	v_add_f32_e32 v130, v123, v129
	v_sub_f32_e32 v131, v116, v130
	v_sub_f32_e32 v116, v116, v131
	v_sub_f32_e32 v123, v130, v123
	v_sub_f32_e32 v116, v116, v130
	v_sub_f32_e32 v123, v123, v129
	v_add_f32_e32 v116, v117, v116
	v_add_f32_e32 v116, v123, v116
	v_add_f32_e32 v117, v131, v116
	v_mul_f32_e32 v123, v126, v117
	v_sub_f32_e32 v129, v131, v117
	v_mul_f32_e32 v130, v125, v123
	v_add_f32_e32 v116, v116, v129
	v_add_f32_e32 v129, v122, v123
	v_fma_f32 v125, v123, v125, -v130
	v_sub_f32_e32 v122, v129, v122
	v_fmac_f32_e32 v125, v123, v115
	v_sub_f32_e32 v115, v123, v122
	v_add_f32_e32 v122, v130, v125
	v_sub_f32_e32 v123, v122, v130
	v_sub_f32_e32 v130, v117, v122
	v_sub_f32_e32 v117, v117, v130
	v_sub_f32_e32 v117, v117, v122
	v_cvt_f32_i32_e32 v114, v114
	v_sub_f32_e32 v123, v123, v125
	v_add_f32_e32 v116, v116, v117
	v_add_f32_e32 v116, v123, v116
	v_add_f32_e32 v116, v130, v116
	v_mul_f32_e32 v116, v126, v116
	v_add_f32_e32 v115, v115, v116
	v_mul_f32_e32 v123, 0x3f317218, v114
	v_add_f32_e32 v116, v129, v115
	v_fma_f32 v125, v114, s71, -v123
; __device__ __forceinline__ unsigned cvt_pk_bf16(float lo, float hi) { unsigned r; asm volatile("v_cvt_pk_bf16_f32 %0, %1, %2" : "=v"(r) : "v"(lo), "v"(hi)); return r; }
; __device__ __forceinline__ float bflo(unsigned w) { return __uint_as_float(w << 16); }
; __device__ __forceinline__ float bfhi(unsigned w) { return __uint_as_float(w & 0xffff0000u); }
; __device__ __forceinline__ float sigm(float x) { return __builtin_amdgcn_rcpf(1.f + __expf(-x)); }
; template <bool PASS2> ...
;     ...
;                 const float ba = pba[cb], bx = pbx[cb], sp = log1pf(__expf(-plm[cb]));
; #pragma unroll
;                 for (int tb = 0; tb < 2; ++tb)
; #pragma unroll
;                     for (int q = 0; q < 4; ++q) { const float xv = xl[(tb * 16 + fq * 4 + q) * 68 + cb * 16 + fr];
;                         const float r = sigm(ga[tb][q] + ba), ig = sigm(gx[tb][q] + bx), la = -8.f * r * sp;
;                         const float aa = __expf(la), om = (1.f - aa) * (1.f + aa), bb = __builtin_amdgcn_sqrtf(om) * (ig * xv);
;                         const unsigned pk = cvt_pk_bf16(la, bb);
;                         labd[(size_t)(tb * 16 + q) * 256 + cb * 16] = pk;
;                         av[tb][q] = __expf(bflo(pk)); bv[tb][q] = bfhi(pk); }
	v_fmac_f32_e32 v125, 0xb102e308, v114
	v_sub_f32_e32 v114, v116, v129
	v_mul_f32_e32 v117, v116, v116
	v_sub_f32_e32 v114, v115, v114
	v_add_f32_e32 v115, v123, v125
	v_fmamk_f32 v122, v117, 0x3e9b6dac, v198
	v_sub_f32_e32 v123, v115, v123
	v_fmaak_f32 v122, v117, v122, 0x3f2aaada
	v_sub_f32_e32 v123, v125, v123
	v_ldexp_f32 v125, v116, 1
	v_mul_f32_e32 v116, v116, v117
	v_mul_f32_e32 v116, v116, v122
	v_add_f32_e32 v117, v125, v116
	v_sub_f32_e32 v122, v117, v125
	v_ldexp_f32 v114, v114, 1
	v_sub_f32_e32 v116, v116, v122
	v_add_f32_e32 v114, v114, v116
	v_add_f32_e32 v116, v117, v114
	v_sub_f32_e32 v117, v116, v117
	v_sub_f32_e32 v114, v114, v117
	v_add_f32_e32 v117, v115, v116
	v_sub_f32_e32 v122, v117, v115
	v_sub_f32_e32 v125, v117, v122
	v_sub_f32_e32 v115, v115, v125
	v_sub_f32_e32 v116, v116, v122
	v_add_f32_e32 v115, v116, v115
	v_add_f32_e32 v116, v123, v114
	v_sub_f32_e32 v122, v116, v123
	v_add_f32_e32 v115, v116, v115
	v_sub_f32_e32 v125, v116, v122
	v_add_f32_e32 v116, v117, v115
	v_sub_f32_e32 v123, v123, v125
	v_sub_f32_e32 v114, v114, v122
	v_sub_f32_e32 v117, v116, v117
	v_add_f32_e32 v114, v114, v123
	v_sub_f32_e32 v115, v115, v117
	v_add_f32_e32 v114, v114, v115
	v_add_f32_e32 v74, 1.0, v74
	v_add_f32_e32 v114, v116, v114
	v_cmp_neq_f32_e32 vcc, s12, v124
	v_rcp_f32_e32 v74, v74
	v_mul_f32_e32 v75, 0xbfb8aa3b, v75
	v_cndmask_b32_e32 v114, v203, v114, vcc
	v_cmp_ngt_f32_e32 vcc, -1.0, v124
	v_mul_f32_e32 v74, 0xc1000000, v74
	v_exp_f32_e32 v75, v75
	v_cndmask_b32_e32 v114, v204, v114, vcc
	v_cmp_neq_f32_e32 vcc, -1.0, v124
	v_add_f32_e32 v82, v128, v82
	v_add_f32_e32 v75, 1.0, v75
	v_cndmask_b32_e32 v114, v205, v114, vcc
	v_cmp_lt_f32_e64 vcc, |v124|, s13
	v_mul_f32_e32 v82, 0xbfb8aa3b, v82
	v_rcp_f32_e32 v75, v75
	v_cndmask_b32_e32 v122, v114, v124, vcc
	v_mul_f32_e32 v74, v74, v122
	v_mul_f32_e32 v114, 0x3fb8aa3b, v74
	v_exp_f32_e32 v114, v114
	v_exp_f32_e32 v82, v82
	v_mul_f32_e32 v75, 0xc1000000, v75
	ds_read_b32 v123, v101
	v_sub_f32_e32 v115, 1.0, v114
	v_add_f32_e32 v114, 1.0, v114
	v_mul_f32_e32 v114, v115, v114
	v_sqrt_f32_e32 v124, v114
	v_mfma_f32_16x16x32_bf16 v[114:117], v[18:21], v[78:81], v[118:121]
	v_add_f32_e32 v79, v128, v83
	v_add_f32_e32 v82, 1.0, v82
	v_mul_f32_e32 v79, 0xbfb8aa3b, v79
	v_mul_f32_e32 v75, v75, v122
	v_rcp_f32_e32 v82, v82
	v_exp_f32_e32 v79, v79
	v_mul_f32_e32 v80, 0x3fb8aa3b, v75
	v_exp_f32_e32 v80, v80
	s_waitcnt lgkmcnt(0)
	v_mul_f32_e32 v78, v123, v82
	v_add_f32_e32 v79, 1.0, v79
	v_mul_f32_e32 v78, v78, v124
	v_cvt_pk_bf16_f32 v74, v74, v78
	ds_read_b32 v81, v101 offset:272
	v_rcp_f32_e32 v82, v79
	v_sub_f32_e32 v79, 1.0, v80
	v_add_f32_e32 v80, 1.0, v80
	v_mul_f32_e32 v79, v79, v80
	v_sqrt_f32_e32 v80, v79
	global_store_dword v[104:105], v74, off
	v_lshlrev_b32_e32 v78, 16, v74
	v_and_b32_e32 v79, 0xffff0000, v74
	s_waitcnt lgkmcnt(0)
	v_mul_f32_e32 v74, v82, v81
	v_mul_f32_e32 v74, v74, v80
	v_cvt_pk_bf16_f32 v74, v75, v74
	v_add_f32_e32 v75, v127, v76
	v_mul_f32_e32 v75, 0xbfb8aa3b, v75
	v_exp_f32_e32 v75, v75
	v_add_f32_e32 v80, v128, v84
	v_mul_f32_e32 v80, 0xbfb8aa3b, v80
	v_exp_f32_e32 v80, v80
	v_add_f32_e32 v75, 1.0, v75
	v_rcp_f32_e32 v75, v75
	ds_read_b32 v82, v101 offset:544
	v_add_f32_e32 v80, 1.0, v80
	v_rcp_f32_e32 v83, v80
	v_mul_f32_e32 v75, 0xc1000000, v75
	v_mul_f32_e32 v75, v75, v122
	v_mul_f32_e32 v81, 0x3fb8aa3b, v75
	v_exp_f32_e32 v81, v81
	global_store_dword v[104:105], v74, off offset:1024
	v_lshlrev_b32_e32 v76, 16, v74
	v_add_f32_e32 v70, v127, v70
	v_sub_f32_e32 v80, 1.0, v81
	v_add_f32_e32 v81, 1.0, v81
	v_mul_f32_e32 v80, v80, v81
	v_sqrt_f32_e32 v81, v80
	v_and_b32_e32 v80, 0xffff0000, v74
	s_waitcnt lgkmcnt(0)
; __device__ __forceinline__ unsigned cvt_pk_bf16(float lo, float hi) { unsigned r; asm volatile("v_cvt_pk_bf16_f32 %0, %1, %2" : "=v"(r) : "v"(lo), "v"(hi)); return r; }
; __device__ __forceinline__ float bflo(unsigned w) { return __uint_as_float(w << 16); }
; __device__ __forceinline__ float bfhi(unsigned w) { return __uint_as_float(w & 0xffff0000u); }
; __device__ __forceinline__ float sigm(float x) { return __builtin_amdgcn_rcpf(1.f + __expf(-x)); }
; template <bool PASS2> ...
;     ...
;                 const float ba = pba[cb], bx = pbx[cb], sp = log1pf(__expf(-plm[cb]));
; #pragma unroll
;                 for (int tb = 0; tb < 2; ++tb)
; #pragma unroll
;                     for (int q = 0; q < 4; ++q) { const float xv = xl[(tb * 16 + fq * 4 + q) * 68 + cb * 16 + fr];
;                         const float r = sigm(ga[tb][q] + ba), ig = sigm(gx[tb][q] + bx), la = -8.f * r * sp;
;                         const float aa = __expf(la), om = (1.f - aa) * (1.f + aa), bb = __builtin_amdgcn_sqrtf(om) * (ig * xv);
;                         const unsigned pk = cvt_pk_bf16(la, bb);
;                         labd[(size_t)(tb * 16 + q) * 256 + cb * 16] = pk;
;                         av[tb][q] = __expf(bflo(pk)); bv[tb][q] = bfhi(pk); }
	v_mul_f32_e32 v74, v83, v82
	v_mul_f32_e32 v70, 0xbfb8aa3b, v70
	v_mul_f32_e32 v74, v74, v81
	v_cvt_pk_bf16_f32 v74, v75, v74
	v_add_f32_e32 v75, v127, v77
	v_mul_f32_e32 v75, 0xbfb8aa3b, v75
	v_exp_f32_e32 v75, v75
	v_add_f32_e32 v81, v128, v85
	v_mul_f32_e32 v81, 0xbfb8aa3b, v81
	v_exp_f32_e32 v81, v81
	v_add_f32_e32 v75, 1.0, v75
	v_rcp_f32_e32 v75, v75
	v_exp_f32_e32 v70, v70
	ds_read_b32 v83, v101 offset:816
	v_add_f32_e32 v81, 1.0, v81
	v_mul_f32_e32 v75, 0xc1000000, v75
	v_mul_f32_e32 v75, v75, v122
	v_mul_f32_e32 v82, 0x3fb8aa3b, v75
	v_exp_f32_e32 v82, v82
	v_rcp_f32_e32 v81, v81
	v_add_f32_e32 v70, 1.0, v70
	v_rcp_f32_e32 v70, v70
	v_sub_f32_e32 v84, 1.0, v82
	v_add_f32_e32 v82, 1.0, v82
	v_mul_f32_e32 v82, v84, v82
	v_sqrt_f32_e32 v82, v82
	s_waitcnt lgkmcnt(0)
	v_mul_f32_e32 v81, v81, v83
	global_store_dword v[104:105], v74, off offset:2048
	v_mul_f32_e32 v70, 0xc1000000, v70
	v_mul_f32_e32 v81, v81, v82
	v_cvt_pk_bf16_f32 v81, v75, v81
	v_add_f32_e32 v75, v128, v114
	v_mul_f32_e32 v75, 0xbfb8aa3b, v75
	v_add_f32_e32 v71, v127, v71
	v_exp_f32_e32 v75, v75
	v_mul_f32_e32 v70, v70, v122
	v_mul_f32_e32 v71, 0xbfb8aa3b, v71
	v_mul_f32_e32 v82, 0x3fb8aa3b, v70
	v_exp_f32_e32 v71, v71
	v_exp_f32_e32 v82, v82
	ds_read_b32 v83, v101 offset:4352
	v_add_f32_e32 v75, 1.0, v75
	v_rcp_f32_e32 v75, v75
	v_add_f32_e32 v71, 1.0, v71
	v_sub_f32_e32 v84, 1.0, v82
	v_add_f32_e32 v82, 1.0, v82
	v_rcp_f32_e32 v71, v71
	v_mul_f32_e32 v82, v84, v82
	v_sqrt_f32_e32 v84, v82
	v_lshlrev_b32_e32 v77, 16, v74
	v_and_b32_e32 v82, 0xffff0000, v74
	s_waitcnt lgkmcnt(0)
	v_mul_f32_e32 v74, v75, v83
	v_add_f32_e32 v83, v128, v115
	v_mul_f32_e32 v83, 0xbfb8aa3b, v83
	v_mul_f32_e32 v71, 0xc1000000, v71
	v_exp_f32_e32 v83, v83
	v_mul_f32_e32 v71, v71, v122
	v_mul_f32_e32 v74, v74, v84
	v_mul_f32_e32 v84, 0x3fb8aa3b, v71
	v_exp_f32_e32 v84, v84
	global_store_dword v[104:105], v81, off offset:3072
	v_cvt_pk_bf16_f32 v70, v70, v74
	ds_read_b32 v85, v101 offset:4624
	v_add_f32_e32 v83, 1.0, v83
	v_rcp_f32_e32 v83, v83
	v_sub_f32_e32 v114, 1.0, v84
	v_add_f32_e32 v84, 1.0, v84
	v_mul_f32_e32 v84, v114, v84
	v_add_f32_e32 v72, v127, v72
	v_sqrt_f32_e32 v84, v84
	v_mul_f32_e32 v72, 0xbfb8aa3b, v72
	s_waitcnt lgkmcnt(0)
	v_mul_f32_e32 v83, v83, v85
	v_exp_f32_e32 v85, v72
	v_add_co_u32_e32 v74, vcc, s0, v104
	v_mul_f32_e32 v72, v83, v84
	s_nop 0
	v_addc_co_u32_e32 v75, vcc, 0, v105, vcc
	global_store_dword v[74:75], v70, off
	v_cvt_pk_bf16_f32 v72, v71, v72
	v_add_f32_e32 v71, 1.0, v85
	v_rcp_f32_e32 v71, v71
	v_add_f32_e32 v83, v128, v116
	v_mul_f32_e32 v83, 0xbfb8aa3b, v83
	v_exp_f32_e32 v83, v83
	v_mul_f32_e32 v71, 0xc1000000, v71
	v_mul_f32_e32 v71, v71, v122
	v_mul_f32_e32 v84, 0x3fb8aa3b, v71
	v_exp_f32_e32 v84, v84
	ds_read_b32 v85, v101 offset:4896
	v_add_f32_e32 v83, 1.0, v83
	v_rcp_f32_e32 v83, v83
	v_sub_f32_e32 v114, 1.0, v84
	v_add_f32_e32 v84, 1.0, v84
	v_mul_f32_e32 v84, v114, v84
	v_add_f32_e32 v73, v127, v73
	v_sqrt_f32_e32 v84, v84
	v_mul_f32_e32 v73, 0xbfb8aa3b, v73
	v_exp_f32_e32 v73, v73
	s_waitcnt lgkmcnt(0)
	v_mul_f32_e32 v83, v83, v85
	v_mul_f32_e32 v83, v83, v84
	global_store_dword v[74:75], v72, off offset:1024
	v_cvt_pk_bf16_f32 v83, v71, v83
	v_add_f32_e32 v71, 1.0, v73
	v_rcp_f32_e32 v71, v71
	v_add_f32_e32 v73, v128, v117
	v_mul_f32_e32 v73, 0xbfb8aa3b, v73
	v_exp_f32_e32 v73, v73
	v_mul_f32_e32 v71, 0xc1000000, v71
	v_mul_f32_e32 v71, v71, v122
	v_mul_f32_e32 v84, 0x3fb8aa3b, v71
	v_exp_f32_e32 v84, v84
	ds_read_b32 v114, v101 offset:5168
	v_add_f32_e32 v73, 1.0, v73
	v_rcp_f32_e32 v73, v73
	v_sub_f32_e32 v85, 1.0, v84
	v_add_f32_e32 v84, 1.0, v84
	v_mul_f32_e32 v84, v85, v84
	v_mul_f32_e32 v78, 0x3fb8aa3b, v78
	v_mul_f32_e32 v76, 0x3fb8aa3b, v76
	v_mul_f32_e32 v77, 0x3fb8aa3b, v77
	v_sqrt_f32_e32 v84, v84
	v_exp_f32_e32 v78, v78
	v_exp_f32_e32 v76, v76
	v_exp_f32_e32 v77, v77
	s_waitcnt lgkmcnt(0)
	v_mul_f32_e32 v73, v73, v114
	v_and_b32_e32 v85, 0xffff0000, v81
	v_mul_f32_e32 v73, v73, v84
	s_and_b64 vcc, exec, s[50:51]
	global_store_dword v[74:75], v83, off offset:2048
	v_cvt_pk_bf16_f32 v84, v71, v73
	global_store_dword v[74:75], v84, off offset:3072
	s_cbranch_vccz .LBB0_741
	v_fma_f32 v71, v77, v85, v82
	v_fma_f32 v71, v76, v71, v80
	v_fma_f32 v73, v78, v71, v79
	s_mov_b64 s[20:21], 0

; template <bool PASS2> ...
;     ...
;             for (int tb = 0; tb < 2; ++tb) {
;                 Ap[tb] = (av[tb][0] * av[tb][1]) * (av[tb][2] * av[tb][3]);
;                 Bp[tb] = d == 0 ? ((bv[tb][0] * av[tb][1] + bv[tb][1]) * av[tb][2] + bv[tb][2]) * av[tb][3] + bv[tb][3]
;                                 : ((bv[tb][3] * av[tb][2] + bv[tb][2]) * av[tb][1] + bv[tb][1]) * av[tb][0] + bv[tb][0];
;             }
;             float PA[8], PB[8];
; #pragma unroll
;             for (int e = 0; e < 8; ++e) { PA[e] = __shfl(Ap[e >> 2], (e & 3) * 16 + fr); PB[e] = __shfl(Bp[e >> 2], (e & 3) * 16 + fr); }
;             const size_t si = ((size_t)(b * NCH + c) * 2 + d) * 256 + chn;
;             if (!PASS2) {
;                 float At = 1.f, Bt = 0.f;
; #pragma unroll
;                 for (int e2 = 0; e2 < 8; ++e2) { const int e = d == 0 ? e2 : 7 - e2; Bt = PA[e] * Bt + PB[e]; At *= PA[e]; }
.LBB0_748:
	v_mul_f32_e32 v70, v79, v70
	v_mul_f32_e32 v72, v72, v80
	v_mul_f32_e32 v82, v70, v72
	v_mul_f32_e32 v70, v78, v76
	v_mul_f32_e32 v71, v77, v71
	v_and_b32_e32 v77, 64, v199
	v_mul_f32_e32 v78, v70, v71
	v_or_b32_e32 v70, v77, v87
	v_or_b32_e32 v77, v77, v95
	v_lshlrev_b32_e32 v76, 2, v70
	v_lshl_or_b32 v77, v77, 2, v206
	ds_bpermute_b32 v83, v76, v78
	ds_bpermute_b32 v70, v76, v73
	ds_bpermute_b32 v116, v76, v78 offset:64
	ds_bpermute_b32 v71, v76, v73 offset:64
	ds_bpermute_b32 v85, v76, v78 offset:128
	ds_bpermute_b32 v72, v76, v73 offset:128
	ds_bpermute_b32 v117, v77, v78
	ds_bpermute_b32 v73, v77, v73
	ds_bpermute_b32 v114, v76, v82
	ds_bpermute_b32 v81, v76, v118
	ds_bpermute_b32 v115, v76, v82 offset:64
	ds_bpermute_b32 v80, v76, v118 offset:64
	ds_bpermute_b32 v84, v76, v82 offset:128
	ds_bpermute_b32 v79, v76, v118 offset:128
	ds_bpermute_b32 v82, v77, v82
	ds_bpermute_b32 v78, v77, v118
	s_mov_b32 s5, s89
	s_lshl_b64 s[4:5], s[4:5], 8
	s_or_b64 s[66:67], s[4:5], s[46:47]
	s_and_saveexec_b64 s[4:5], s[36:37]
	s_cbranch_execz .LBB0_750
	s_cmp_eq_u32 s64, 1
	s_cselect_b64 vcc, -1, 0
	s_cmp_eq_u32 s64, 2
	s_waitcnt lgkmcnt(0)
	v_cndmask_b32_e32 v120, v83, v116, vcc
	s_cselect_b64 vcc, -1, 0
	s_cmp_eq_u32 s64, 3
	v_cndmask_b32_e32 v120, v120, v85, vcc
	s_cselect_b64 vcc, -1, 0
	s_cmp_eq_u32 s64, 4
	v_cndmask_b32_e32 v120, v120, v117, vcc
	s_cselect_b64 vcc, -1, 0
	s_cmp_eq_u32 s64, 5
	v_cndmask_b32_e32 v120, v120, v114, vcc
	s_cselect_b64 vcc, -1, 0
	s_cmp_eq_u32 s64, 6
	v_cndmask_b32_e32 v120, v120, v115, vcc
	s_cselect_b64 vcc, -1, 0
	s_cmp_eq_u32 s64, 7
	v_cndmask_b32_e32 v120, v120, v84, vcc
	s_cselect_b64 vcc, -1, 0
	s_cmp_eq_u32 s62, 1
	v_cndmask_b32_e32 v120, v120, v82, vcc
	s_cselect_b64 vcc, -1, 0
	s_cmp_eq_u32 s62, 2
	v_cndmask_b32_e32 v121, v83, v116, vcc
	s_cselect_b64 vcc, -1, 0
	s_cmp_eq_u32 s62, 3
	v_cndmask_b32_e32 v121, v121, v85, vcc
	s_cselect_b64 vcc, -1, 0
	s_cmp_eq_u32 s62, 4
	v_cndmask_b32_e32 v121, v121, v117, vcc
	s_cselect_b64 vcc, -1, 0
	s_cmp_eq_u32 s62, 5
	v_cndmask_b32_e32 v121, v121, v114, vcc
	s_cselect_b64 vcc, -1, 0
	s_cmp_eq_u32 s62, 6
	v_cndmask_b32_e32 v121, v121, v115, vcc
	s_cselect_b64 vcc, -1, 0
	s_cmp_eq_u32 s62, 7
	v_cndmask_b32_e32 v121, v121, v84, vcc
	s_cselect_b64 vcc, -1, 0
	s_cmp_eq_u32 s60, 1
	v_cndmask_b32_e32 v121, v121, v82, vcc
	s_cselect_b64 vcc, -1, 0
	s_cmp_eq_u32 s60, 2
	v_cndmask_b32_e32 v123, v83, v116, vcc
	s_cselect_b64 vcc, -1, 0
	s_cmp_eq_u32 s60, 3
	v_cndmask_b32_e32 v123, v123, v85, vcc
	s_cselect_b64 vcc, -1, 0
	s_cmp_eq_u32 s60, 4
	v_cndmask_b32_e32 v123, v123, v117, vcc
	s_cselect_b64 vcc, -1, 0
	s_cmp_eq_u32 s60, 5
	v_cndmask_b32_e32 v123, v123, v114, vcc
	s_cselect_b64 vcc, -1, 0
	s_cmp_eq_u32 s60, 6
	v_cndmask_b32_e32 v123, v123, v115, vcc
	s_cselect_b64 vcc, -1, 0
	s_cmp_eq_u32 s60, 7
	v_cndmask_b32_e32 v123, v123, v84, vcc
	s_cselect_b64 vcc, -1, 0
	s_cmp_eq_u32 s58, 1
	v_cndmask_b32_e32 v123, v123, v82, vcc
	s_cselect_b64 vcc, -1, 0
	s_cmp_eq_u32 s58, 2
	v_cndmask_b32_e32 v124, v83, v116, vcc
	s_cselect_b64 vcc, -1, 0
	s_cmp_eq_u32 s58, 3
	v_cndmask_b32_e32 v124, v124, v85, vcc
	s_cselect_b64 vcc, -1, 0
	s_cmp_eq_u32 s58, 4
	v_cndmask_b32_e32 v124, v124, v117, vcc
	s_cselect_b64 vcc, -1, 0
	s_cmp_eq_u32 s58, 5
	v_cndmask_b32_e32 v124, v124, v114, vcc
	s_cselect_b64 vcc, -1, 0
	s_cmp_eq_u32 s58, 6
	v_cndmask_b32_e32 v124, v124, v115, vcc
	s_cselect_b64 vcc, -1, 0
	s_cmp_eq_u32 s58, 7
	v_cndmask_b32_e32 v124, v124, v84, vcc
	s_cselect_b64 vcc, -1, 0
	s_cmp_eq_u32 s56, 1
	v_cndmask_b32_e32 v124, v124, v82, vcc
	s_cselect_b64 vcc, -1, 0
	s_cmp_eq_u32 s56, 2
	v_cndmask_b32_e32 v125, v83, v116, vcc
	s_cselect_b64 vcc, -1, 0
	s_cmp_eq_u32 s56, 3
	v_cndmask_b32_e32 v125, v125, v85, vcc
	s_cselect_b64 vcc, -1, 0
	s_cmp_eq_u32 s56, 4
	v_cndmask_b32_e32 v125, v125, v117, vcc
	s_cselect_b64 vcc, -1, 0
	s_cmp_eq_u32 s56, 5
	v_cndmask_b32_e32 v125, v125, v114, vcc
	s_cselect_b64 vcc, -1, 0
	s_cmp_eq_u32 s56, 6
	v_cndmask_b32_e32 v125, v125, v115, vcc
	s_cselect_b64 vcc, -1, 0
	s_cmp_eq_u32 s56, 7
	v_cndmask_b32_e32 v125, v125, v84, vcc
	s_cselect_b64 vcc, -1, 0
	s_cmp_eq_u32 s54, 1
	v_cndmask_b32_e32 v125, v125, v82, vcc
	s_cselect_b64 vcc, -1, 0
	s_cmp_eq_u32 s54, 2
	v_cndmask_b32_e32 v126, v83, v116, vcc
	s_cselect_b64 vcc, -1, 0
	s_cmp_eq_u32 s54, 3
	v_cndmask_b32_e32 v126, v126, v85, vcc
	s_cselect_b64 vcc, -1, 0
	s_cmp_eq_u32 s54, 4
	v_cndmask_b32_e32 v126, v126, v117, vcc
	s_cselect_b64 vcc, -1, 0
	s_cmp_eq_u32 s54, 5
	v_cndmask_b32_e32 v126, v126, v114, vcc
	s_cselect_b64 vcc, -1, 0
	s_cmp_eq_u32 s54, 6
	v_cndmask_b32_e32 v126, v126, v115, vcc
	s_cselect_b64 vcc, -1, 0
	s_cmp_eq_u32 s54, 7
	v_cndmask_b32_e32 v126, v126, v84, vcc
	s_cselect_b64 vcc, -1, 0
	s_cmp_eq_u32 s52, 1
	v_cndmask_b32_e32 v126, v126, v82, vcc
	s_cselect_b64 vcc, -1, 0
	s_cmp_eq_u32 s52, 2
	v_cndmask_b32_e32 v127, v83, v116, vcc
	s_cselect_b64 vcc, -1, 0
	s_cmp_eq_u32 s52, 3
	v_cndmask_b32_e32 v127, v127, v85, vcc
	s_cselect_b64 vcc, -1, 0
	s_cmp_eq_u32 s52, 4
	v_cndmask_b32_e32 v127, v127, v117, vcc
	s_cselect_b64 vcc, -1, 0
	s_cmp_eq_u32 s52, 5
	v_cndmask_b32_e32 v127, v127, v114, vcc
	s_cselect_b64 vcc, -1, 0
	s_cmp_eq_u32 s52, 6
	v_cndmask_b32_e32 v127, v127, v115, vcc
	s_cselect_b64 vcc, -1, 0
	s_cmp_eq_u32 s52, 7
	v_cndmask_b32_e32 v127, v127, v84, vcc
	s_cselect_b64 vcc, -1, 0
	s_cmp_eq_u32 s50, 1
	v_cndmask_b32_e32 v127, v127, v82, vcc
	s_cselect_b64 vcc, -1, 0
	s_cmp_eq_u32 s50, 2
	v_cndmask_b32_e32 v83, v83, v116, vcc
	s_cselect_b64 vcc, -1, 0
	s_cmp_eq_u32 s50, 3
	v_cndmask_b32_e32 v83, v83, v85, vcc
	s_cselect_b64 vcc, -1, 0
	s_cmp_eq_u32 s50, 4
	v_cndmask_b32_e32 v83, v83, v117, vcc
; __device__ __forceinline__ float sigm(float x) { return __builtin_amdgcn_rcpf(1.f + __expf(-x)); }
; #define MFMA16(a, b, c) __builtin_amdgcn_mfma_f32_16x16x32_bf16((a), (b), (c), 0, 0, 0)
; template <bool PASS2> ...
;     ...
;                 for (int ks = 0; ks < 2; ++ks) {
; #pragma unroll
;                     for (int tb = 0; tb < 2; ++tb) { ga[tb] = MFMA16(af[tb][ks], wfa[cb][ks], ga[tb]); gx[tb] = MFMA16(af[tb][ks], wfx[cb][ks], gx[tb]); } }
;                 const float ba = pba[cb], bx = pbx[cb], sp = log1pf(__expf(-plm[cb]));
; #pragma unroll
;                 for (int tb = 0; tb < 2; ++tb)
; #pragma unroll
;                     for (int q = 0; q < 4; ++q) { const float xv = xl[(tb * 16 + fq * 4 + q) * 68 + cb * 16 + fr];
;                         const float r = sigm(ga[tb][q] + ba), ig = sigm(gx[tb][q] + bx), la = -8.f * r * sp;
;                         const float aa = __expf(la), om = (1.f - aa) * (1.f + aa), bb = __builtin_amdgcn_sqrtf(om) * (ig * xv);
;     ...
;                 float At = 1.f, Bt = 0.f;
; #pragma unroll
;                 for (int e2 = 0; e2 < 8; ++e2) { const int e = d == 0 ? e2 : 7 - e2; Bt = PA[e] * Bt + PB[e]; At *= PA[e]; }
;                 if (fq == 0) { LRA[si] = At; LRB[si] = Bt; }
	s_cselect_b64 vcc, -1, 0
	s_cmp_eq_u32 s50, 5
	v_cndmask_b32_e32 v83, v83, v114, vcc
	s_cselect_b64 vcc, -1, 0
	s_cmp_eq_u32 s50, 6
	v_cndmask_b32_e32 v83, v83, v115, vcc
	s_cselect_b64 vcc, -1, 0
	v_cndmask_b32_e32 v83, v83, v84, vcc
	v_cndmask_b32_e64 v84, v78, v70, s[48:49]
	v_fmac_f32_e32 v84, 0, v120
	v_cndmask_b32_e64 v85, v79, v71, s[48:49]
	v_fmac_f32_e32 v85, v121, v84
	v_cndmask_b32_e64 v84, v80, v72, s[48:49]
	v_mul_f32_e32 v122, v120, v121
	v_fmac_f32_e32 v84, v123, v85
	v_cndmask_b32_e64 v85, v81, v73, s[48:49]
	v_mul_f32_e32 v122, v123, v122
	v_fmac_f32_e32 v85, v124, v84
	v_cndmask_b32_e64 v73, v73, v81, s[48:49]
	v_mul_f32_e32 v122, v124, v122
	s_cmp_eq_u32 s50, 7
	v_fmac_f32_e32 v73, v125, v85
	v_cndmask_b32_e64 v72, v72, v80, s[48:49]
	v_mul_f32_e32 v122, v125, v122
	s_cselect_b64 vcc, -1, 0
	v_fmac_f32_e32 v72, v126, v73
	v_cndmask_b32_e64 v71, v71, v79, s[48:49]
	v_mov_b32_e32 v119, s67
	v_or_b32_e32 v118, s66, v94
	v_mul_f32_e32 v122, v126, v122
	v_cndmask_b32_e32 v82, v83, v82, vcc
	v_fmac_f32_e32 v71, v127, v72
	v_cndmask_b32_e64 v78, v70, v78, s[48:49]
	v_mul_f32_e32 v122, v127, v122
	v_fmac_f32_e32 v78, v82, v71
	v_lshlrev_b64 v[70:71], 2, v[118:119]
	v_mul_f32_e32 v83, v82, v122
	v_lshl_add_u64 v[72:73], s[44:45], 0, v[70:71]
	v_lshl_add_u64 v[70:71], s[42:43], 0, v[70:71]
	global_store_dword v[70:71], v83, off
	global_store_dword v[72:73], v78, off
.LBB0_750:
	s_or_b64 exec, exec, s[4:5]
	s_waitcnt lgkmcnt(0)
	v_mfma_f32_16x16x32_bf16 v[70:73], v[2:5], v[58:61], 0
	s_mov_b64 s[4:5], -1
	v_mfma_f32_16x16x32_bf16 v[78:81], v[2:5], v[66:69], 0
	v_mfma_f32_16x16x32_bf16 v[58:61], v[14:17], v[58:61], 0
	v_mfma_f32_16x16x32_bf16 v[82:85], v[14:17], v[66:69], 0
	v_mfma_f32_16x16x32_bf16 v[70:73], v[6:9], v[54:57], v[70:73]
	v_mfma_f32_16x16x32_bf16 v[66:69], v[6:9], v[62:65], v[78:81]
	v_mfma_f32_16x16x32_bf16 v[58:61], v[18:21], v[54:57], v[58:61]
	v_mfma_f32_16x16x32_bf16 v[54:57], v[18:21], v[62:65], v[82:85]
	v_mul_f32_e32 v62, 0xbfb8aa3b, v113
	v_exp_f32_e32 v64, v62
	s_nop 3
	v_add_f32_e32 v67, v111, v67
	v_mul_f32_e32 v67, 0xbfb8aa3b, v67
	v_exp_f32_e32 v67, v67
	v_add_f32_e32 v65, 1.0, v64
	v_add_f32_e32 v62, -1.0, v65
	v_sub_f32_e32 v63, v62, v65
	v_add_f32_e32 v63, 1.0, v63
	v_sub_f32_e32 v62, v64, v62
	v_add_f32_e32 v78, v62, v63
	v_frexp_mant_f32_e32 v62, v65
	v_cmp_gt_f32_e32 vcc, s70, v62
	v_cvt_f64_f32_e32 v[62:63], v65
	v_frexp_exp_i32_f64_e32 v62, v[62:63]
	v_subbrev_co_u32_e32 v62, vcc, 0, v62, vcc
	v_sub_u32_e32 v63, 0, v62
	v_ldexp_f32 v65, v65, v63
	v_ldexp_f32 v63, v78, v63
	v_add_f32_e32 v78, -1.0, v65
	v_add_f32_e32 v79, 1.0, v78
	v_sub_f32_e32 v79, v65, v79
	v_add_f32_e32 v79, v63, v79
	v_add_f32_e32 v80, v78, v79
	v_sub_f32_e32 v78, v80, v78
	v_sub_f32_e32 v78, v79, v78
	v_add_f32_e32 v79, 1.0, v65
	v_add_f32_e32 v81, -1.0, v79
	v_sub_f32_e32 v65, v65, v81
	v_add_f32_e32 v63, v63, v65
	v_add_f32_e32 v65, v79, v63
	v_sub_f32_e32 v79, v65, v79
	v_sub_f32_e32 v63, v63, v79
	v_rcp_f32_e32 v79, v65
	v_cvt_f32_i32_e32 v62, v62
	v_cmp_neq_f32_e32 vcc, s12, v64
	v_add_f32_e32 v67, 1.0, v67
	v_mul_f32_e32 v81, v80, v79
	v_mul_f32_e32 v82, v65, v81
	v_fma_f32 v83, v81, v65, -v82
	v_fmac_f32_e32 v83, v81, v63
	v_add_f32_e32 v84, v82, v83
	v_sub_f32_e32 v85, v80, v84
	v_sub_f32_e32 v80, v80, v85
	v_sub_f32_e32 v82, v84, v82
	v_sub_f32_e32 v80, v80, v84
	v_add_f32_e32 v78, v78, v80
	v_sub_f32_e32 v80, v82, v83
	v_add_f32_e32 v78, v80, v78
	v_add_f32_e32 v80, v85, v78
	v_mul_f32_e32 v82, v79, v80
	v_mul_f32_e32 v83, v65, v82
	v_fma_f32 v65, v82, v65, -v83
	v_fmac_f32_e32 v65, v82, v63
	v_sub_f32_e32 v63, v85, v80
	v_add_f32_e32 v63, v78, v63
	v_add_f32_e32 v78, v83, v65
	v_sub_f32_e32 v84, v80, v78
	v_sub_f32_e32 v80, v80, v84
	v_sub_f32_e32 v83, v78, v83
	v_sub_f32_e32 v78, v80, v78
	v_add_f32_e32 v63, v63, v78
	v_sub_f32_e32 v65, v83, v65
	v_add_f32_e32 v63, v65, v63
	v_add_f32_e32 v65, v81, v82
	v_add_f32_e32 v63, v84, v63
	v_sub_f32_e32 v78, v65, v81
	v_mul_f32_e32 v63, v79, v63
	v_sub_f32_e32 v78, v82, v78
	v_add_f32_e32 v63, v78, v63
	v_mul_f32_e32 v81, 0x3f317218, v62
	v_add_f32_e32 v78, v65, v63
	v_fma_f32 v82, v62, s71, -v81
	v_mul_f32_e32 v79, v78, v78
	v_fmac_f32_e32 v82, 0xb102e308, v62
	v_sub_f32_e32 v62, v78, v65
	v_fmamk_f32 v80, v79, 0x3e9b6dac, v198
	v_sub_f32_e32 v62, v63, v62
	v_add_f32_e32 v63, v81, v82
	v_fmaak_f32 v80, v79, v80, 0x3f2aaada
	v_sub_f32_e32 v65, v63, v81
	v_ldexp_f32 v81, v78, 1
	v_mul_f32_e32 v78, v78, v79
	v_mul_f32_e32 v78, v78, v80
	v_add_f32_e32 v79, v81, v78
	v_sub_f32_e32 v80, v79, v81
	v_ldexp_f32 v62, v62, 1
	v_sub_f32_e32 v78, v78, v80
	v_add_f32_e32 v62, v62, v78
	v_add_f32_e32 v78, v79, v62
	v_sub_f32_e32 v79, v78, v79
	v_sub_f32_e32 v62, v62, v79
	v_add_f32_e32 v79, v63, v78
	v_sub_f32_e32 v80, v79, v63
	v_sub_f32_e32 v81, v79, v80
	v_sub_f32_e32 v65, v82, v65
	v_sub_f32_e32 v63, v63, v81
	v_sub_f32_e32 v78, v78, v80
	v_add_f32_e32 v63, v78, v63
	v_add_f32_e32 v78, v65, v62
	v_sub_f32_e32 v80, v78, v65
	v_sub_f32_e32 v81, v78, v80
	v_sub_f32_e32 v65, v65, v81
	v_sub_f32_e32 v62, v62, v80
	v_add_f32_e32 v63, v78, v63
	v_add_f32_e32 v62, v62, v65
	v_add_f32_e32 v65, v79, v63
	v_sub_f32_e32 v78, v65, v79
	v_sub_f32_e32 v63, v63, v78
	v_add_f32_e32 v62, v62, v63
	v_add_f32_e32 v62, v65, v62
	v_cndmask_b32_e32 v62, v203, v62, vcc
	v_cmp_ngt_f32_e32 vcc, -1.0, v64
	v_add_f32_e32 v65, v111, v66
	v_mul_f32_e32 v65, 0xbfb8aa3b, v65
	v_cndmask_b32_e32 v62, v204, v62, vcc
	v_cmp_neq_f32_e32 vcc, -1.0, v64
	v_exp_f32_e32 v65, v65
	v_rcp_f32_e32 v67, v67
	v_cndmask_b32_e32 v62, v205, v62, vcc
	v_cmp_lt_f32_e64 vcc, |v64|, s13
	v_add_f32_e32 v65, 1.0, v65
	v_rcp_f32_e32 v65, v65
	v_cndmask_b32_e32 v63, v62, v64, vcc
	v_add_f32_e32 v64, v112, v70
	v_mul_f32_e32 v64, 0xbfb8aa3b, v64
	v_exp_f32_e32 v64, v64
	ds_read_b32 v62, v101 offset:64
	v_add_f32_e32 v68, v111, v68
	v_mul_f32_e32 v68, 0xbfb8aa3b, v68
	v_add_f32_e32 v64, 1.0, v64
	v_rcp_f32_e32 v64, v64
	s_waitcnt lgkmcnt(0)
; __device__ __forceinline__ unsigned cvt_pk_bf16(float lo, float hi) { unsigned r; asm volatile("v_cvt_pk_bf16_f32 %0, %1, %2" : "=v"(r) : "v"(lo), "v"(hi)); return r; }
; __device__ __forceinline__ float bflo(unsigned w) { return __uint_as_float(w << 16); }
; __device__ __forceinline__ float bfhi(unsigned w) { return __uint_as_float(w & 0xffff0000u); }
; __device__ __forceinline__ float sigm(float x) { return __builtin_amdgcn_rcpf(1.f + __expf(-x)); }
; template <bool PASS2> ...
;     ...
;                     for (int q = 0; q < 4; ++q) { const float xv = xl[(tb * 16 + fq * 4 + q) * 68 + cb * 16 + fr];
;                         const float r = sigm(ga[tb][q] + ba), ig = sigm(gx[tb][q] + bx), la = -8.f * r * sp;
;                         const float aa = __expf(la), om = (1.f - aa) * (1.f + aa), bb = __builtin_amdgcn_sqrtf(om) * (ig * xv);
;                         const unsigned pk = cvt_pk_bf16(la, bb);
;                         labd[(size_t)(tb * 16 + q) * 256 + cb * 16] = pk;
;                         av[tb][q] = __expf(bflo(pk)); bv[tb][q] = bfhi(pk); }
	v_mul_f32_e32 v62, v62, v65
	v_exp_f32_e32 v68, v68
	v_add_f32_e32 v58, v112, v58
	v_mul_f32_e32 v64, 0xc1000000, v64
	v_mul_f32_e32 v64, v63, v64
	v_mul_f32_e32 v66, 0x3fb8aa3b, v64
	v_exp_f32_e32 v66, v66
	v_add_f32_e32 v68, 1.0, v68
	v_rcp_f32_e32 v68, v68
	v_add_f32_e32 v69, v111, v69
	v_sub_f32_e32 v70, 1.0, v66
	v_add_f32_e32 v66, 1.0, v66
	v_mul_f32_e32 v66, v70, v66
	v_sqrt_f32_e32 v66, v66
	v_mul_f32_e32 v58, 0xbfb8aa3b, v58
	v_mul_f32_e32 v69, 0xbfb8aa3b, v69
	v_exp_f32_e32 v58, v58
	v_mul_f32_e32 v62, v62, v66
	v_add_f32_e32 v66, v112, v71
	v_mul_f32_e32 v66, 0xbfb8aa3b, v66
	v_exp_f32_e32 v66, v66
	v_cvt_pk_bf16_f32 v64, v64, v62
	ds_read_b32 v65, v101 offset:336
	global_store_dword v[104:105], v64, off offset:64
	v_add_f32_e32 v66, 1.0, v66
	v_rcp_f32_e32 v66, v66
	v_exp_f32_e32 v69, v69
	s_waitcnt lgkmcnt(0)
	v_mul_f32_e32 v65, v67, v65
	v_add_f32_e32 v58, 1.0, v58
	v_mul_f32_e32 v66, 0xc1000000, v66
	v_mul_f32_e32 v66, v63, v66
	v_mul_f32_e32 v70, 0x3fb8aa3b, v66
	v_exp_f32_e32 v70, v70
	v_add_f32_e32 v69, 1.0, v69
	v_rcp_f32_e32 v58, v58
	v_add_f32_e32 v59, v112, v59
	v_sub_f32_e32 v71, 1.0, v70
	v_add_f32_e32 v70, 1.0, v70
	v_mul_f32_e32 v70, v71, v70
	v_sqrt_f32_e32 v70, v70
	v_rcp_f32_e32 v69, v69
	v_mul_f32_e32 v59, 0xbfb8aa3b, v59
	v_add_f32_e32 v54, v111, v54
	v_mul_f32_e32 v65, v65, v70
	v_add_f32_e32 v70, v112, v72
	v_mul_f32_e32 v70, 0xbfb8aa3b, v70
	v_exp_f32_e32 v70, v70
	v_cvt_pk_bf16_f32 v66, v66, v65
	ds_read_b32 v67, v101 offset:608
	global_store_dword v[104:105], v66, off offset:1088
	v_add_f32_e32 v70, 1.0, v70
	v_rcp_f32_e32 v70, v70
	v_exp_f32_e32 v59, v59
	s_waitcnt lgkmcnt(0)
	v_mul_f32_e32 v67, v68, v67
	v_mul_f32_e32 v54, 0xbfb8aa3b, v54
	v_mul_f32_e32 v70, 0xc1000000, v70
	v_mul_f32_e32 v70, v63, v70
	v_mul_f32_e32 v71, 0x3fb8aa3b, v70
	v_exp_f32_e32 v71, v71
	v_exp_f32_e32 v54, v54
	v_mul_f32_e32 v58, 0xc1000000, v58
	v_mul_f32_e32 v58, v63, v58
	v_sub_f32_e32 v72, 1.0, v71
	v_add_f32_e32 v71, 1.0, v71
	v_mul_f32_e32 v71, v72, v71
	v_sqrt_f32_e32 v71, v71
	v_add_f32_e32 v59, 1.0, v59
	v_rcp_f32_e32 v59, v59
	v_add_f32_e32 v54, 1.0, v54
	v_mul_f32_e32 v67, v67, v71
	v_add_f32_e32 v71, v112, v73
	v_mul_f32_e32 v71, 0xbfb8aa3b, v71
	v_exp_f32_e32 v71, v71
	v_cvt_pk_bf16_f32 v68, v70, v67
	ds_read_b32 v70, v101 offset:880
	global_store_dword v[104:105], v68, off offset:2112
	v_add_f32_e32 v71, 1.0, v71
	v_rcp_f32_e32 v71, v71
	v_rcp_f32_e32 v54, v54
	s_waitcnt lgkmcnt(0)
	v_mul_f32_e32 v69, v69, v70
	v_mul_f32_e32 v59, 0xc1000000, v59
	v_mul_f32_e32 v71, 0xc1000000, v71
	v_mul_f32_e32 v71, v63, v71
	v_mul_f32_e32 v72, 0x3fb8aa3b, v71
	v_exp_f32_e32 v72, v72
	v_add_f32_e32 v55, v111, v55
	v_mul_f32_e32 v59, v63, v59
	v_mul_f32_e32 v55, 0xbfb8aa3b, v55
	v_sub_f32_e32 v73, 1.0, v72
	v_add_f32_e32 v72, 1.0, v72
	v_mul_f32_e32 v72, v73, v72
	v_sqrt_f32_e32 v72, v72
	v_exp_f32_e32 v55, v55
	v_add_f32_e32 v56, v111, v56
	v_mul_f32_e32 v56, 0xbfb8aa3b, v56
	v_mul_f32_e32 v69, v72, v69
	v_mul_f32_e32 v72, 0x3fb8aa3b, v58
	v_exp_f32_e32 v72, v72
	v_cvt_pk_bf16_f32 v70, v71, v69
	ds_read_b32 v71, v101 offset:4416
	global_store_dword v[104:105], v70, off offset:3136
	v_sub_f32_e32 v73, 1.0, v72
	v_add_f32_e32 v72, 1.0, v72
	v_mul_f32_e32 v72, v73, v72
	v_sqrt_f32_e32 v72, v72
	s_waitcnt lgkmcnt(0)
	v_mul_f32_e32 v54, v54, v71
	v_mul_f32_e32 v71, 0x3fb8aa3b, v59
	v_exp_f32_e32 v71, v71
	v_mul_f32_e32 v54, v72, v54
	v_cvt_pk_bf16_f32 v54, v58, v54
	ds_read_b32 v58, v101 offset:4688
	v_add_f32_e32 v55, 1.0, v55
	v_sub_f32_e32 v72, 1.0, v71
	v_add_f32_e32 v71, 1.0, v71
	v_rcp_f32_e32 v55, v55
	v_mul_f32_e32 v71, v72, v71
	v_sqrt_f32_e32 v71, v71
	global_store_dword v[74:75], v54, off offset:64
	s_waitcnt lgkmcnt(0)
	v_mul_f32_e32 v55, v55, v58
	v_exp_f32_e32 v56, v56
	v_mul_f32_e32 v55, v71, v55
	v_cvt_pk_bf16_f32 v55, v59, v55
	v_add_f32_e32 v59, v112, v60
	v_mul_f32_e32 v59, 0xbfb8aa3b, v59
	v_exp_f32_e32 v59, v59
	ds_read_b32 v58, v101 offset:4960
	v_add_f32_e32 v56, 1.0, v56
	v_rcp_f32_e32 v56, v56
	v_add_f32_e32 v59, 1.0, v59
	v_rcp_f32_e32 v59, v59
	global_store_dword v[74:75], v55, off offset:1088
	s_waitcnt lgkmcnt(0)
	v_mul_f32_e32 v56, v56, v58
	v_add_f32_e32 v57, v111, v57
	v_mul_f32_e32 v59, 0xc1000000, v59
	v_mul_f32_e32 v59, v63, v59
	v_mul_f32_e32 v60, 0x3fb8aa3b, v59
	v_exp_f32_e32 v60, v60
	v_mul_f32_e32 v57, 0xbfb8aa3b, v57
	v_exp_f32_e32 v57, v57
	v_lshlrev_b32_e32 v62, 16, v64
	v_sub_f32_e32 v71, 1.0, v60
	v_add_f32_e32 v60, 1.0, v60
	v_mul_f32_e32 v60, v71, v60
	v_sqrt_f32_e32 v60, v60
	v_add_f32_e32 v57, 1.0, v57
	v_lshlrev_b32_e32 v65, 16, v66
	v_lshlrev_b32_e32 v67, 16, v68
	v_mul_f32_e32 v56, v60, v56
	v_cvt_pk_bf16_f32 v56, v59, v56
	v_add_f32_e32 v59, v112, v61
	v_mul_f32_e32 v59, 0xbfb8aa3b, v59
	v_exp_f32_e32 v59, v59
	ds_read_b32 v58, v101 offset:5232
	v_rcp_f32_e32 v57, v57
	v_mul_f32_e32 v62, 0x3fb8aa3b, v62
	v_add_f32_e32 v59, 1.0, v59
	v_rcp_f32_e32 v59, v59
	v_mul_f32_e32 v65, 0x3fb8aa3b, v65
	v_mul_f32_e32 v67, 0x3fb8aa3b, v67
	v_exp_f32_e32 v62, v62
	v_mul_f32_e32 v59, 0xc1000000, v59
	v_mul_f32_e32 v59, v63, v59
	v_mul_f32_e32 v60, 0x3fb8aa3b, v59
	v_exp_f32_e32 v60, v60
	v_exp_f32_e32 v65, v65
	v_exp_f32_e32 v67, v67
	s_waitcnt lgkmcnt(0)
	v_mul_f32_e32 v57, v57, v58
	v_sub_f32_e32 v61, 1.0, v60
	v_add_f32_e32 v60, 1.0, v60
	v_mul_f32_e32 v60, v61, v60
	v_sqrt_f32_e32 v60, v60
	v_and_b32_e32 v64, 0xffff0000, v64
	v_and_b32_e32 v66, 0xffff0000, v66
	v_and_b32_e32 v68, 0xffff0000, v68
	v_and_b32_e32 v69, 0xffff0000, v70
	v_mul_f32_e32 v57, v60, v57
	s_and_b64 vcc, exec, s[38:39]
	global_store_dword v[74:75], v56, off offset:2112
	v_cvt_pk_bf16_f32 v58, v59, v57
	global_store_dword v[74:75], v58, off offset:3136
	s_cbranch_vccnz .LBB0_752
	v_fma_f32 v57, v67, v69, v68
	v_fma_f32 v57, v65, v57, v66
	v_fma_f32 v57, v62, v57, v64
	s_mov_b64 s[4:5], 0

; __device__ __forceinline__ float sigm(float x) { return __builtin_amdgcn_rcpf(1.f + __expf(-x)); }
; #define MFMA16(a, b, c) __builtin_amdgcn_mfma_f32_16x16x32_bf16((a), (b), (c), 0, 0, 0)
; template <bool PASS2> ...
;     ...
;                 for (int ks = 0; ks < 2; ++ks) {
; #pragma unroll
;                     for (int tb = 0; tb < 2; ++tb) { ga[tb] = MFMA16(af[tb][ks], wfa[cb][ks], ga[tb]); gx[tb] = MFMA16(af[tb][ks], wfx[cb][ks], gx[tb]); } }
;                 const float ba = pba[cb], bx = pbx[cb], sp = log1pf(__expf(-plm[cb]));
; #pragma unroll
;                 for (int tb = 0; tb < 2; ++tb)
; #pragma unroll
;                     for (int q = 0; q < 4; ++q) { const float xv = xl[(tb * 16 + fq * 4 + q) * 68 + cb * 16 + fr];
;                         const float r = sigm(ga[tb][q] + ba), ig = sigm(gx[tb][q] + bx), la = -8.f * r * sp;
;                         const float aa = __expf(la), om = (1.f - aa) * (1.f + aa), bb = __builtin_amdgcn_sqrtf(om) * (ig * xv);
.LBB0_760:
	s_or_b64 exec, exec, s[4:5]
	s_waitcnt lgkmcnt(0)
	v_mfma_f32_16x16x32_bf16 v[54:57], v[2:5], v[46:49], 0
	s_mov_b64 s[4:5], -1
	v_mfma_f32_16x16x32_bf16 v[60:63], v[2:5], v[50:53], 0
	v_mfma_f32_16x16x32_bf16 v[46:49], v[14:17], v[46:49], 0
	v_mfma_f32_16x16x32_bf16 v[64:67], v[14:17], v[50:53], 0
	v_mfma_f32_16x16x32_bf16 v[54:57], v[6:9], v[38:41], v[54:57]
	v_mfma_f32_16x16x32_bf16 v[50:53], v[6:9], v[42:45], v[60:63]
	v_mfma_f32_16x16x32_bf16 v[46:49], v[18:21], v[38:41], v[46:49]
	v_mfma_f32_16x16x32_bf16 v[38:41], v[18:21], v[42:45], v[64:67]
	v_mul_f32_e32 v42, 0xbfb8aa3b, v110
	v_exp_f32_e32 v44, v42
	s_nop 3
	v_add_f32_e32 v51, v108, v51
	v_mul_f32_e32 v51, 0xbfb8aa3b, v51
	v_exp_f32_e32 v51, v51
	v_add_f32_e32 v45, 1.0, v44
	v_add_f32_e32 v42, -1.0, v45
	v_sub_f32_e32 v43, v42, v45
	v_add_f32_e32 v43, 1.0, v43
	v_sub_f32_e32 v42, v44, v42
	v_add_f32_e32 v60, v42, v43
	v_frexp_mant_f32_e32 v42, v45
	v_cmp_gt_f32_e32 vcc, s70, v42
	v_cvt_f64_f32_e32 v[42:43], v45
	v_frexp_exp_i32_f64_e32 v42, v[42:43]
	v_subbrev_co_u32_e32 v42, vcc, 0, v42, vcc
	v_sub_u32_e32 v43, 0, v42
	v_ldexp_f32 v45, v45, v43
	v_ldexp_f32 v43, v60, v43
	v_add_f32_e32 v60, -1.0, v45
	v_add_f32_e32 v61, 1.0, v60
	v_sub_f32_e32 v61, v45, v61
	v_add_f32_e32 v61, v43, v61
	v_add_f32_e32 v62, v60, v61
	v_sub_f32_e32 v60, v62, v60
	v_sub_f32_e32 v60, v61, v60
	v_add_f32_e32 v61, 1.0, v45
	v_add_f32_e32 v63, -1.0, v61
	v_sub_f32_e32 v45, v45, v63
	v_add_f32_e32 v43, v43, v45
	v_add_f32_e32 v45, v61, v43
	v_sub_f32_e32 v61, v45, v61
	v_sub_f32_e32 v43, v43, v61
	v_rcp_f32_e32 v61, v45
	v_cvt_f32_i32_e32 v42, v42
	v_cmp_neq_f32_e32 vcc, s12, v44
	v_add_f32_e32 v51, 1.0, v51
	v_mul_f32_e32 v63, v62, v61
	v_mul_f32_e32 v64, v45, v63
	v_fma_f32 v65, v63, v45, -v64
	v_fmac_f32_e32 v65, v63, v43
	v_add_f32_e32 v66, v64, v65
	v_sub_f32_e32 v67, v62, v66
	v_sub_f32_e32 v62, v62, v67
	v_sub_f32_e32 v64, v66, v64
	v_sub_f32_e32 v62, v62, v66
	v_add_f32_e32 v60, v60, v62
	v_sub_f32_e32 v62, v64, v65
	v_add_f32_e32 v60, v62, v60
	v_add_f32_e32 v62, v67, v60
	v_mul_f32_e32 v64, v61, v62
	v_mul_f32_e32 v65, v45, v64
	v_fma_f32 v45, v64, v45, -v65
	v_fmac_f32_e32 v45, v64, v43
	v_sub_f32_e32 v43, v67, v62
	v_add_f32_e32 v43, v60, v43
	v_add_f32_e32 v60, v65, v45
	v_sub_f32_e32 v66, v62, v60
	v_sub_f32_e32 v62, v62, v66
	v_sub_f32_e32 v65, v60, v65
	v_sub_f32_e32 v60, v62, v60
	v_add_f32_e32 v43, v43, v60
	v_sub_f32_e32 v45, v65, v45
	v_add_f32_e32 v43, v45, v43
	v_add_f32_e32 v45, v63, v64
	v_add_f32_e32 v43, v66, v43
	v_sub_f32_e32 v60, v45, v63
	v_mul_f32_e32 v43, v61, v43
	v_sub_f32_e32 v60, v64, v60
	v_add_f32_e32 v43, v60, v43
	v_mul_f32_e32 v63, 0x3f317218, v42
	v_add_f32_e32 v60, v45, v43
	v_fma_f32 v64, v42, s71, -v63
	v_mul_f32_e32 v61, v60, v60
	v_fmac_f32_e32 v64, 0xb102e308, v42
	v_sub_f32_e32 v42, v60, v45
	v_fmamk_f32 v62, v61, 0x3e9b6dac, v198
	v_sub_f32_e32 v42, v43, v42
	v_add_f32_e32 v43, v63, v64
	v_fmaak_f32 v62, v61, v62, 0x3f2aaada
	v_sub_f32_e32 v45, v43, v63
	v_ldexp_f32 v63, v60, 1
	v_mul_f32_e32 v60, v60, v61
	v_mul_f32_e32 v60, v60, v62
	v_add_f32_e32 v61, v63, v60
	v_sub_f32_e32 v62, v61, v63
	v_ldexp_f32 v42, v42, 1
	v_sub_f32_e32 v60, v60, v62
	v_add_f32_e32 v42, v42, v60
	v_add_f32_e32 v60, v61, v42
	v_sub_f32_e32 v61, v60, v61
	v_sub_f32_e32 v42, v42, v61
	v_add_f32_e32 v61, v43, v60
	v_sub_f32_e32 v62, v61, v43
	v_sub_f32_e32 v63, v61, v62
	v_sub_f32_e32 v45, v64, v45
	v_sub_f32_e32 v43, v43, v63
	v_sub_f32_e32 v60, v60, v62
	v_add_f32_e32 v43, v60, v43
	v_add_f32_e32 v60, v45, v42
	v_sub_f32_e32 v62, v60, v45
	v_sub_f32_e32 v63, v60, v62
	v_sub_f32_e32 v45, v45, v63
	v_sub_f32_e32 v42, v42, v62
	v_add_f32_e32 v43, v60, v43
	v_add_f32_e32 v42, v42, v45
	v_add_f32_e32 v45, v61, v43
	v_sub_f32_e32 v60, v45, v61
	v_sub_f32_e32 v43, v43, v60
	v_add_f32_e32 v42, v42, v43
	v_add_f32_e32 v42, v45, v42
	v_cndmask_b32_e32 v42, v203, v42, vcc
	v_cmp_ngt_f32_e32 vcc, -1.0, v44
	v_add_f32_e32 v45, v108, v50
	v_mul_f32_e32 v45, 0xbfb8aa3b, v45
	v_cndmask_b32_e32 v42, v204, v42, vcc
	v_cmp_neq_f32_e32 vcc, -1.0, v44
	v_exp_f32_e32 v45, v45
	v_rcp_f32_e32 v51, v51
	v_cndmask_b32_e32 v42, v205, v42, vcc
	v_cmp_lt_f32_e64 vcc, |v44|, s13
	v_add_f32_e32 v45, 1.0, v45
	v_rcp_f32_e32 v45, v45
	v_cndmask_b32_e32 v43, v42, v44, vcc
	v_add_f32_e32 v44, v109, v54
	v_mul_f32_e32 v44, 0xbfb8aa3b, v44
	v_exp_f32_e32 v44, v44
	ds_read_b32 v42, v101 offset:128
	v_add_f32_e32 v52, v108, v52
	v_mul_f32_e32 v52, 0xbfb8aa3b, v52
	v_add_f32_e32 v44, 1.0, v44
	v_rcp_f32_e32 v44, v44
	s_waitcnt lgkmcnt(0)
	v_mul_f32_e32 v42, v42, v45
	v_exp_f32_e32 v52, v52
	v_add_f32_e32 v46, v109, v46
	v_mul_f32_e32 v44, 0xc1000000, v44
	v_mul_f32_e32 v44, v43, v44
	v_mul_f32_e32 v50, 0x3fb8aa3b, v44
	v_exp_f32_e32 v50, v50
	v_add_f32_e32 v52, 1.0, v52
	v_rcp_f32_e32 v52, v52
	v_add_f32_e32 v53, v108, v53
	v_sub_f32_e32 v54, 1.0, v50
	v_add_f32_e32 v50, 1.0, v50
	v_mul_f32_e32 v50, v54, v50
	v_sqrt_f32_e32 v50, v50
	v_mul_f32_e32 v46, 0xbfb8aa3b, v46
	v_mul_f32_e32 v53, 0xbfb8aa3b, v53
	v_exp_f32_e32 v46, v46
	v_mul_f32_e32 v42, v42, v50
	v_add_f32_e32 v50, v109, v55
	v_mul_f32_e32 v50, 0xbfb8aa3b, v50
	v_exp_f32_e32 v50, v50
	v_cvt_pk_bf16_f32 v44, v44, v42
	ds_read_b32 v45, v101 offset:400
	global_store_dword v[104:105], v44, off offset:128
	v_add_f32_e32 v50, 1.0, v50
	v_rcp_f32_e32 v50, v50
	v_exp_f32_e32 v53, v53
	s_waitcnt lgkmcnt(0)
; __device__ __forceinline__ unsigned cvt_pk_bf16(float lo, float hi) { unsigned r; asm volatile("v_cvt_pk_bf16_f32 %0, %1, %2" : "=v"(r) : "v"(lo), "v"(hi)); return r; }
; __device__ __forceinline__ float bflo(unsigned w) { return __uint_as_float(w << 16); }
; __device__ __forceinline__ float bfhi(unsigned w) { return __uint_as_float(w & 0xffff0000u); }
; __device__ __forceinline__ float sigm(float x) { return __builtin_amdgcn_rcpf(1.f + __expf(-x)); }
; template <bool PASS2> ...
;     ...
;                     for (int q = 0; q < 4; ++q) { const float xv = xl[(tb * 16 + fq * 4 + q) * 68 + cb * 16 + fr];
;                         const float r = sigm(ga[tb][q] + ba), ig = sigm(gx[tb][q] + bx), la = -8.f * r * sp;
;                         const float aa = __expf(la), om = (1.f - aa) * (1.f + aa), bb = __builtin_amdgcn_sqrtf(om) * (ig * xv);
;                         const unsigned pk = cvt_pk_bf16(la, bb);
;                         labd[(size_t)(tb * 16 + q) * 256 + cb * 16] = pk;
;                         av[tb][q] = __expf(bflo(pk)); bv[tb][q] = bfhi(pk); }
	v_mul_f32_e32 v45, v51, v45
	v_add_f32_e32 v46, 1.0, v46
	v_mul_f32_e32 v50, 0xc1000000, v50
	v_mul_f32_e32 v50, v43, v50
	v_mul_f32_e32 v54, 0x3fb8aa3b, v50
	v_exp_f32_e32 v54, v54
	v_add_f32_e32 v53, 1.0, v53
	v_rcp_f32_e32 v46, v46
	v_add_f32_e32 v47, v109, v47
	v_sub_f32_e32 v55, 1.0, v54
	v_add_f32_e32 v54, 1.0, v54
	v_mul_f32_e32 v54, v55, v54
	v_sqrt_f32_e32 v54, v54
	v_rcp_f32_e32 v53, v53
	v_mul_f32_e32 v47, 0xbfb8aa3b, v47
	v_add_f32_e32 v38, v108, v38
	v_mul_f32_e32 v45, v45, v54
	v_add_f32_e32 v54, v109, v56
	v_mul_f32_e32 v54, 0xbfb8aa3b, v54
	v_exp_f32_e32 v54, v54
	v_cvt_pk_bf16_f32 v50, v50, v45
	ds_read_b32 v51, v101 offset:672
	global_store_dword v[104:105], v50, off offset:1152
	v_add_f32_e32 v54, 1.0, v54
	v_rcp_f32_e32 v54, v54
	v_exp_f32_e32 v47, v47
	s_waitcnt lgkmcnt(0)
	v_mul_f32_e32 v51, v52, v51
	v_mul_f32_e32 v38, 0xbfb8aa3b, v38
	v_mul_f32_e32 v54, 0xc1000000, v54
	v_mul_f32_e32 v54, v43, v54
	v_mul_f32_e32 v55, 0x3fb8aa3b, v54
	v_exp_f32_e32 v55, v55
	v_exp_f32_e32 v38, v38
	v_mul_f32_e32 v46, 0xc1000000, v46
	v_mul_f32_e32 v46, v43, v46
	v_sub_f32_e32 v56, 1.0, v55
	v_add_f32_e32 v55, 1.0, v55
	v_mul_f32_e32 v55, v56, v55
	v_sqrt_f32_e32 v55, v55
	v_add_f32_e32 v47, 1.0, v47
	v_rcp_f32_e32 v47, v47
	v_add_f32_e32 v38, 1.0, v38
	v_mul_f32_e32 v51, v51, v55
	v_add_f32_e32 v55, v109, v57
	v_mul_f32_e32 v55, 0xbfb8aa3b, v55
	v_exp_f32_e32 v55, v55
	v_cvt_pk_bf16_f32 v52, v54, v51
	ds_read_b32 v54, v101 offset:944
	global_store_dword v[104:105], v52, off offset:2176
	v_add_f32_e32 v55, 1.0, v55
	v_rcp_f32_e32 v55, v55
	v_rcp_f32_e32 v38, v38
	s_waitcnt lgkmcnt(0)
	v_mul_f32_e32 v53, v53, v54
	v_mul_f32_e32 v47, 0xc1000000, v47
	v_mul_f32_e32 v55, 0xc1000000, v55
	v_mul_f32_e32 v55, v43, v55
	v_mul_f32_e32 v56, 0x3fb8aa3b, v55
	v_exp_f32_e32 v56, v56
	v_add_f32_e32 v39, v108, v39
	v_mul_f32_e32 v47, v43, v47
	v_mul_f32_e32 v39, 0xbfb8aa3b, v39
	v_sub_f32_e32 v57, 1.0, v56
	v_add_f32_e32 v56, 1.0, v56
	v_mul_f32_e32 v56, v57, v56
	v_sqrt_f32_e32 v56, v56
	v_exp_f32_e32 v39, v39
	v_add_f32_e32 v40, v108, v40
	v_mul_f32_e32 v40, 0xbfb8aa3b, v40
	v_mul_f32_e32 v53, v56, v53
	v_mul_f32_e32 v56, 0x3fb8aa3b, v46
	v_exp_f32_e32 v56, v56
	v_cvt_pk_bf16_f32 v54, v55, v53
	ds_read_b32 v55, v101 offset:4480
	global_store_dword v[104:105], v54, off offset:3200
	v_sub_f32_e32 v57, 1.0, v56
	v_add_f32_e32 v56, 1.0, v56
	v_mul_f32_e32 v56, v57, v56
	v_sqrt_f32_e32 v56, v56
	s_waitcnt lgkmcnt(0)
	v_mul_f32_e32 v38, v38, v55
	v_mul_f32_e32 v55, 0x3fb8aa3b, v47
	v_exp_f32_e32 v55, v55
	v_mul_f32_e32 v38, v56, v38
	v_cvt_pk_bf16_f32 v38, v46, v38
	ds_read_b32 v46, v101 offset:4752
	v_add_f32_e32 v39, 1.0, v39
	v_sub_f32_e32 v56, 1.0, v55
	v_add_f32_e32 v55, 1.0, v55
	v_rcp_f32_e32 v39, v39
	v_mul_f32_e32 v55, v56, v55
	v_sqrt_f32_e32 v55, v55
	global_store_dword v[74:75], v38, off offset:128
	s_waitcnt lgkmcnt(0)
	v_mul_f32_e32 v39, v39, v46
	v_exp_f32_e32 v40, v40
	v_mul_f32_e32 v39, v55, v39
	v_cvt_pk_bf16_f32 v39, v47, v39
	v_add_f32_e32 v47, v109, v48
	v_mul_f32_e32 v47, 0xbfb8aa3b, v47
	v_exp_f32_e32 v47, v47
	ds_read_b32 v46, v101 offset:5024
	v_add_f32_e32 v40, 1.0, v40
	v_rcp_f32_e32 v40, v40
	v_add_f32_e32 v47, 1.0, v47
	v_rcp_f32_e32 v47, v47
	global_store_dword v[74:75], v39, off offset:1152
	s_waitcnt lgkmcnt(0)
	v_mul_f32_e32 v40, v40, v46
	v_add_f32_e32 v41, v108, v41
	v_mul_f32_e32 v47, 0xc1000000, v47
	v_mul_f32_e32 v47, v43, v47
	v_mul_f32_e32 v48, 0x3fb8aa3b, v47
	v_exp_f32_e32 v48, v48
	v_mul_f32_e32 v41, 0xbfb8aa3b, v41
	v_exp_f32_e32 v41, v41
	v_lshlrev_b32_e32 v42, 16, v44
	v_sub_f32_e32 v55, 1.0, v48
	v_add_f32_e32 v48, 1.0, v48
	v_mul_f32_e32 v48, v55, v48
	v_sqrt_f32_e32 v48, v48
	v_add_f32_e32 v41, 1.0, v41
	v_lshlrev_b32_e32 v45, 16, v50
	v_lshlrev_b32_e32 v51, 16, v52
	v_mul_f32_e32 v40, v48, v40
	v_cvt_pk_bf16_f32 v40, v47, v40
	v_add_f32_e32 v47, v109, v49
	v_mul_f32_e32 v47, 0xbfb8aa3b, v47
	v_exp_f32_e32 v47, v47
	ds_read_b32 v46, v101 offset:5296
	v_rcp_f32_e32 v41, v41
	v_mul_f32_e32 v42, 0x3fb8aa3b, v42
	v_add_f32_e32 v47, 1.0, v47
	v_rcp_f32_e32 v47, v47
	v_mul_f32_e32 v45, 0x3fb8aa3b, v45
	v_mul_f32_e32 v51, 0x3fb8aa3b, v51
	v_exp_f32_e32 v42, v42
	v_mul_f32_e32 v47, 0xc1000000, v47
	v_mul_f32_e32 v43, v43, v47
	v_mul_f32_e32 v47, 0x3fb8aa3b, v43
	v_exp_f32_e32 v47, v47
	v_exp_f32_e32 v45, v45
	v_exp_f32_e32 v51, v51
	s_waitcnt lgkmcnt(0)
	v_mul_f32_e32 v41, v41, v46
	v_sub_f32_e32 v48, 1.0, v47
	v_add_f32_e32 v47, 1.0, v47
	v_mul_f32_e32 v47, v48, v47
	v_sqrt_f32_e32 v47, v47
	v_and_b32_e32 v44, 0xffff0000, v44
	v_and_b32_e32 v50, 0xffff0000, v50
	v_and_b32_e32 v52, 0xffff0000, v52
	v_and_b32_e32 v53, 0xffff0000, v54
	v_mul_f32_e32 v41, v47, v41
	s_and_b64 vcc, exec, s[38:39]
	global_store_dword v[74:75], v40, off offset:2176
	v_cvt_pk_bf16_f32 v43, v43, v41
	global_store_dword v[74:75], v43, off offset:3200
	s_cbranch_vccnz .LBB0_762
	v_fma_f32 v41, v51, v53, v52
	v_fma_f32 v41, v45, v41, v50
	v_fma_f32 v41, v42, v41, v44
	s_mov_b64 s[4:5], 0

; __device__ __forceinline__ unsigned cvt_pk_bf16(float lo, float hi) { unsigned r; asm volatile("v_cvt_pk_bf16_f32 %0, %1, %2" : "=v"(r) : "v"(lo), "v"(hi)); return r; }
; __device__ __forceinline__ float bflo(unsigned w) { return __uint_as_float(w << 16); }
; __device__ __forceinline__ float bfhi(unsigned w) { return __uint_as_float(w & 0xffff0000u); }
; __device__ __forceinline__ float sigm(float x) { return __builtin_amdgcn_rcpf(1.f + __expf(-x)); }
; #define MFMA16(a, b, c) __builtin_amdgcn_mfma_f32_16x16x32_bf16((a), (b), (c), 0, 0, 0)
; template <bool PASS2> ...
;     ...
;                 f32x4 ga[2], gx[2];
;                 ga[0] = ga[1] = gx[0] = gx[1] = (f32x4){0.f, 0.f, 0.f, 0.f};
; #pragma unroll
;                 for (int ks = 0; ks < 2; ++ks) {
; #pragma unroll
;                     for (int tb = 0; tb < 2; ++tb) { ga[tb] = MFMA16(af[tb][ks], wfa[cb][ks], ga[tb]); gx[tb] = MFMA16(af[tb][ks], wfx[cb][ks], gx[tb]); } }
;                 const float ba = pba[cb], bx = pbx[cb], sp = log1pf(__expf(-plm[cb]));
; #pragma unroll
;                 for (int tb = 0; tb < 2; ++tb)
; #pragma unroll
;                     for (int q = 0; q < 4; ++q) { const float xv = xl[(tb * 16 + fq * 4 + q) * 68 + cb * 16 + fr];
;                         const float r = sigm(ga[tb][q] + ba), ig = sigm(gx[tb][q] + bx), la = -8.f * r * sp;
;                         const float aa = __expf(la), om = (1.f - aa) * (1.f + aa), bb = __builtin_amdgcn_sqrtf(om) * (ig * xv);
;                         const unsigned pk = cvt_pk_bf16(la, bb);
;                         labd[(size_t)(tb * 16 + q) * 256 + cb * 16] = pk;
;                         av[tb][q] = __expf(bflo(pk)); bv[tb][q] = bfhi(pk); }
.LBB0_770:
	s_or_b64 exec, exec, s[4:5]
	s_waitcnt lgkmcnt(0)
	v_mfma_f32_16x16x32_bf16 v[38:41], v[2:5], v[30:33], 0
	s_mov_b64 s[4:5], -1
	v_mfma_f32_16x16x32_bf16 v[42:45], v[2:5], v[34:37], 0
	v_mfma_f32_16x16x32_bf16 v[30:33], v[14:17], v[30:33], 0
	v_mfma_f32_16x16x32_bf16 v[46:49], v[14:17], v[34:37], 0
	v_mfma_f32_16x16x32_bf16 v[38:41], v[6:9], v[22:25], v[38:41]
	v_mfma_f32_16x16x32_bf16 v[34:37], v[6:9], v[26:29], v[42:45]
	v_mfma_f32_16x16x32_bf16 v[30:33], v[18:21], v[22:25], v[30:33]
	v_mfma_f32_16x16x32_bf16 v[22:25], v[18:21], v[26:29], v[46:49]
	v_mul_f32_e32 v26, 0xbfb8aa3b, v107
	v_exp_f32_e32 v28, v26
	s_nop 3
	v_add_f32_e32 v35, v0, v35
	v_mul_f32_e32 v35, 0xbfb8aa3b, v35
	v_exp_f32_e32 v35, v35
	v_add_f32_e32 v29, 1.0, v28
	v_add_f32_e32 v26, -1.0, v29
	v_sub_f32_e32 v27, v26, v29
	v_add_f32_e32 v27, 1.0, v27
	v_sub_f32_e32 v26, v28, v26
	v_add_f32_e32 v42, v26, v27
	v_frexp_mant_f32_e32 v26, v29
	v_cmp_gt_f32_e32 vcc, s70, v26
	v_cvt_f64_f32_e32 v[26:27], v29
	v_frexp_exp_i32_f64_e32 v26, v[26:27]
	v_subbrev_co_u32_e32 v26, vcc, 0, v26, vcc
	v_sub_u32_e32 v27, 0, v26
	v_ldexp_f32 v29, v29, v27
	v_ldexp_f32 v27, v42, v27
	v_add_f32_e32 v42, -1.0, v29
	v_add_f32_e32 v43, 1.0, v42
	v_sub_f32_e32 v43, v29, v43
	v_add_f32_e32 v43, v27, v43
	v_add_f32_e32 v44, v42, v43
	v_sub_f32_e32 v42, v44, v42
	v_sub_f32_e32 v42, v43, v42
	v_add_f32_e32 v43, 1.0, v29
	v_add_f32_e32 v45, -1.0, v43
	v_sub_f32_e32 v29, v29, v45
	v_add_f32_e32 v27, v27, v29
	v_add_f32_e32 v29, v43, v27
	v_sub_f32_e32 v43, v29, v43
	v_sub_f32_e32 v27, v27, v43
	v_rcp_f32_e32 v43, v29
	v_cvt_f32_i32_e32 v26, v26
	v_cmp_neq_f32_e32 vcc, s12, v28
	v_add_f32_e32 v35, 1.0, v35
	v_mul_f32_e32 v45, v44, v43
	v_mul_f32_e32 v46, v29, v45
	v_fma_f32 v47, v45, v29, -v46
	v_fmac_f32_e32 v47, v45, v27
	v_add_f32_e32 v48, v46, v47
	v_sub_f32_e32 v49, v44, v48
	v_sub_f32_e32 v44, v44, v49
	v_sub_f32_e32 v46, v48, v46
	v_sub_f32_e32 v44, v44, v48
	v_add_f32_e32 v42, v42, v44
	v_sub_f32_e32 v44, v46, v47
	v_add_f32_e32 v42, v44, v42
	v_add_f32_e32 v44, v49, v42
	v_mul_f32_e32 v46, v43, v44
	v_mul_f32_e32 v47, v29, v46
	v_fma_f32 v29, v46, v29, -v47
	v_fmac_f32_e32 v29, v46, v27
	v_sub_f32_e32 v27, v49, v44
	v_add_f32_e32 v27, v42, v27
	v_add_f32_e32 v42, v47, v29
	v_sub_f32_e32 v48, v44, v42
	v_sub_f32_e32 v44, v44, v48
	v_sub_f32_e32 v47, v42, v47
	v_sub_f32_e32 v42, v44, v42
	v_add_f32_e32 v27, v27, v42
	v_sub_f32_e32 v29, v47, v29
	v_add_f32_e32 v27, v29, v27
	v_add_f32_e32 v29, v45, v46
	v_add_f32_e32 v27, v48, v27
	v_sub_f32_e32 v42, v29, v45
	v_mul_f32_e32 v27, v43, v27
	v_sub_f32_e32 v42, v46, v42
	v_add_f32_e32 v27, v42, v27
	v_mul_f32_e32 v45, 0x3f317218, v26
	v_add_f32_e32 v42, v29, v27
	v_fma_f32 v46, v26, s71, -v45
	v_mul_f32_e32 v43, v42, v42
	v_fmac_f32_e32 v46, 0xb102e308, v26
	v_sub_f32_e32 v26, v42, v29
	v_fmamk_f32 v44, v43, 0x3e9b6dac, v198
	v_sub_f32_e32 v26, v27, v26
	v_add_f32_e32 v27, v45, v46
	v_fmaak_f32 v44, v43, v44, 0x3f2aaada
	v_sub_f32_e32 v29, v27, v45
	v_ldexp_f32 v45, v42, 1
	v_mul_f32_e32 v42, v42, v43
	v_mul_f32_e32 v42, v42, v44
	v_add_f32_e32 v43, v45, v42
	v_sub_f32_e32 v44, v43, v45
	v_ldexp_f32 v26, v26, 1
	v_sub_f32_e32 v42, v42, v44
	v_add_f32_e32 v26, v26, v42
	v_add_f32_e32 v42, v43, v26
	v_sub_f32_e32 v43, v42, v43
	v_sub_f32_e32 v26, v26, v43
	v_add_f32_e32 v43, v27, v42
	v_sub_f32_e32 v44, v43, v27
	v_sub_f32_e32 v45, v43, v44
	v_sub_f32_e32 v29, v46, v29
	v_sub_f32_e32 v27, v27, v45
	v_sub_f32_e32 v42, v42, v44
	v_add_f32_e32 v27, v42, v27
	v_add_f32_e32 v42, v29, v26
	v_sub_f32_e32 v44, v42, v29
	v_sub_f32_e32 v45, v42, v44
	v_sub_f32_e32 v29, v29, v45
	v_sub_f32_e32 v26, v26, v44
	v_add_f32_e32 v27, v42, v27
	v_add_f32_e32 v26, v26, v29
	v_add_f32_e32 v29, v43, v27
	v_sub_f32_e32 v42, v29, v43
	v_sub_f32_e32 v27, v27, v42
	v_add_f32_e32 v26, v26, v27
	v_add_f32_e32 v26, v29, v26
	v_cndmask_b32_e32 v26, v203, v26, vcc
	v_cmp_ngt_f32_e32 vcc, -1.0, v28
	v_add_f32_e32 v29, v0, v34
	v_mul_f32_e32 v29, 0xbfb8aa3b, v29
	v_cndmask_b32_e32 v26, v204, v26, vcc
	v_cmp_neq_f32_e32 vcc, -1.0, v28
	v_exp_f32_e32 v29, v29
	v_rcp_f32_e32 v35, v35
	v_cndmask_b32_e32 v26, v205, v26, vcc
	v_cmp_lt_f32_e64 vcc, |v28|, s13
	v_add_f32_e32 v29, 1.0, v29
	v_rcp_f32_e32 v29, v29
	v_cndmask_b32_e32 v27, v26, v28, vcc
	v_add_f32_e32 v28, v106, v38
	v_mul_f32_e32 v28, 0xbfb8aa3b, v28
	v_exp_f32_e32 v28, v28
	ds_read_b32 v26, v101 offset:192
	v_add_f32_e32 v36, v0, v36
	v_mul_f32_e32 v36, 0xbfb8aa3b, v36
	v_add_f32_e32 v28, 1.0, v28
	v_rcp_f32_e32 v28, v28
	s_waitcnt lgkmcnt(0)
	v_mul_f32_e32 v26, v26, v29
	v_exp_f32_e32 v36, v36
	v_add_f32_e32 v30, v106, v30
	v_mul_f32_e32 v28, 0xc1000000, v28
	v_mul_f32_e32 v28, v27, v28
	v_mul_f32_e32 v34, 0x3fb8aa3b, v28
	v_exp_f32_e32 v34, v34
	v_add_f32_e32 v36, 1.0, v36
	v_rcp_f32_e32 v36, v36
	v_add_f32_e32 v37, v0, v37
	v_sub_f32_e32 v38, 1.0, v34
	v_add_f32_e32 v34, 1.0, v34
	v_mul_f32_e32 v34, v38, v34
	v_sqrt_f32_e32 v34, v34
	v_mul_f32_e32 v30, 0xbfb8aa3b, v30
	v_mul_f32_e32 v37, 0xbfb8aa3b, v37
	v_exp_f32_e32 v30, v30
	v_mul_f32_e32 v26, v26, v34
	v_add_f32_e32 v34, v106, v39
	v_mul_f32_e32 v34, 0xbfb8aa3b, v34
	v_exp_f32_e32 v34, v34
	v_cvt_pk_bf16_f32 v28, v28, v26
	ds_read_b32 v29, v101 offset:464
	global_store_dword v[104:105], v28, off offset:192
	v_add_f32_e32 v34, 1.0, v34
	v_rcp_f32_e32 v34, v34
	v_exp_f32_e32 v37, v37
	s_waitcnt lgkmcnt(0)
; __device__ __forceinline__ unsigned cvt_pk_bf16(float lo, float hi) { unsigned r; asm volatile("v_cvt_pk_bf16_f32 %0, %1, %2" : "=v"(r) : "v"(lo), "v"(hi)); return r; }
; __device__ __forceinline__ float bflo(unsigned w) { return __uint_as_float(w << 16); }
; __device__ __forceinline__ float bfhi(unsigned w) { return __uint_as_float(w & 0xffff0000u); }
; __device__ __forceinline__ float sigm(float x) { return __builtin_amdgcn_rcpf(1.f + __expf(-x)); }
; template <bool PASS2> ...
;     ...
;                 for (int tb = 0; tb < 2; ++tb)
; #pragma unroll
;                     for (int q = 0; q < 4; ++q) { const float xv = xl[(tb * 16 + fq * 4 + q) * 68 + cb * 16 + fr];
;                         const float r = sigm(ga[tb][q] + ba), ig = sigm(gx[tb][q] + bx), la = -8.f * r * sp;
;                         const float aa = __expf(la), om = (1.f - aa) * (1.f + aa), bb = __builtin_amdgcn_sqrtf(om) * (ig * xv);
;                         const unsigned pk = cvt_pk_bf16(la, bb);
;                         labd[(size_t)(tb * 16 + q) * 256 + cb * 16] = pk;
;                         av[tb][q] = __expf(bflo(pk)); bv[tb][q] = bfhi(pk); }
;             } else {
; #pragma unroll
;                 for (int tb = 0; tb < 2; ++tb)
; #pragma unroll
;                     for (int q = 0; q < 4; ++q) { const unsigned pk = pkv[cb][tb][q]; av[tb][q] = __expf(bflo(pk)); bv[tb][q] = bfhi(pk); }
;             }
; #pragma unroll
;             for (int tb = 0; tb < 2; ++tb) {
;                 Ap[tb] = (av[tb][0] * av[tb][1]) * (av[tb][2] * av[tb][3]);
;                 Bp[tb] = d == 0 ? ((bv[tb][0] * av[tb][1] + bv[tb][1]) * av[tb][2] + bv[tb][2]) * av[tb][3] + bv[tb][3]
;                                 : ((bv[tb][3] * av[tb][2] + bv[tb][2]) * av[tb][1] + bv[tb][1]) * av[tb][0] + bv[tb][0];
	v_mul_f32_e32 v29, v35, v29
	v_add_f32_e32 v30, 1.0, v30
	v_mul_f32_e32 v34, 0xc1000000, v34
	v_mul_f32_e32 v34, v27, v34
	v_mul_f32_e32 v38, 0x3fb8aa3b, v34
	v_exp_f32_e32 v38, v38
	v_add_f32_e32 v37, 1.0, v37
	v_rcp_f32_e32 v30, v30
	v_add_f32_e32 v31, v106, v31
	v_sub_f32_e32 v39, 1.0, v38
	v_add_f32_e32 v38, 1.0, v38
	v_mul_f32_e32 v38, v39, v38
	v_sqrt_f32_e32 v38, v38
	v_rcp_f32_e32 v37, v37
	v_mul_f32_e32 v31, 0xbfb8aa3b, v31
	v_add_f32_e32 v22, v0, v22
	v_mul_f32_e32 v29, v29, v38
	v_add_f32_e32 v38, v106, v40
	v_mul_f32_e32 v38, 0xbfb8aa3b, v38
	v_exp_f32_e32 v38, v38
	v_cvt_pk_bf16_f32 v34, v34, v29
	ds_read_b32 v35, v101 offset:736
	global_store_dword v[104:105], v34, off offset:1216
	v_add_f32_e32 v38, 1.0, v38
	v_rcp_f32_e32 v38, v38
	v_exp_f32_e32 v31, v31
	s_waitcnt lgkmcnt(0)
	v_mul_f32_e32 v35, v36, v35
	v_mul_f32_e32 v22, 0xbfb8aa3b, v22
	v_mul_f32_e32 v38, 0xc1000000, v38
	v_mul_f32_e32 v38, v27, v38
	v_mul_f32_e32 v39, 0x3fb8aa3b, v38
	v_exp_f32_e32 v39, v39
	v_exp_f32_e32 v22, v22
	v_mul_f32_e32 v30, 0xc1000000, v30
	v_mul_f32_e32 v30, v27, v30
	v_sub_f32_e32 v40, 1.0, v39
	v_add_f32_e32 v39, 1.0, v39
	v_mul_f32_e32 v39, v40, v39
	v_sqrt_f32_e32 v39, v39
	v_add_f32_e32 v31, 1.0, v31
	v_rcp_f32_e32 v31, v31
	v_add_f32_e32 v22, 1.0, v22
	v_mul_f32_e32 v35, v35, v39
	v_add_f32_e32 v39, v106, v41
	v_mul_f32_e32 v39, 0xbfb8aa3b, v39
	v_exp_f32_e32 v39, v39
	v_cvt_pk_bf16_f32 v36, v38, v35
	ds_read_b32 v38, v101 offset:1008
	global_store_dword v[104:105], v36, off offset:2240
	v_add_f32_e32 v39, 1.0, v39
	v_rcp_f32_e32 v39, v39
	v_rcp_f32_e32 v22, v22
	s_waitcnt lgkmcnt(0)
	v_mul_f32_e32 v37, v37, v38
	v_mul_f32_e32 v31, 0xc1000000, v31
	v_mul_f32_e32 v39, 0xc1000000, v39
	v_mul_f32_e32 v39, v27, v39
	v_mul_f32_e32 v40, 0x3fb8aa3b, v39
	v_exp_f32_e32 v40, v40
	v_add_f32_e32 v23, v0, v23
	v_mul_f32_e32 v31, v27, v31
	v_mul_f32_e32 v23, 0xbfb8aa3b, v23
	v_sub_f32_e32 v41, 1.0, v40
	v_add_f32_e32 v40, 1.0, v40
	v_mul_f32_e32 v40, v41, v40
	v_sqrt_f32_e32 v40, v40
	v_exp_f32_e32 v23, v23
	v_add_f32_e32 v24, v0, v24
	v_mul_f32_e32 v24, 0xbfb8aa3b, v24
	v_mul_f32_e32 v37, v40, v37
	v_mul_f32_e32 v40, 0x3fb8aa3b, v30
	v_exp_f32_e32 v40, v40
	v_cvt_pk_bf16_f32 v38, v39, v37
	ds_read_b32 v39, v101 offset:4544
	global_store_dword v[104:105], v38, off offset:3264
	v_sub_f32_e32 v41, 1.0, v40
	v_add_f32_e32 v40, 1.0, v40
	v_mul_f32_e32 v40, v41, v40
	v_sqrt_f32_e32 v40, v40
	s_waitcnt lgkmcnt(0)
	v_mul_f32_e32 v22, v22, v39
	v_mul_f32_e32 v39, 0x3fb8aa3b, v31
	v_exp_f32_e32 v39, v39
	v_mul_f32_e32 v22, v40, v22
	v_cvt_pk_bf16_f32 v22, v30, v22
	ds_read_b32 v30, v101 offset:4816
	v_add_f32_e32 v23, 1.0, v23
	v_sub_f32_e32 v40, 1.0, v39
	v_add_f32_e32 v39, 1.0, v39
	v_rcp_f32_e32 v23, v23
	v_mul_f32_e32 v39, v40, v39
	v_sqrt_f32_e32 v39, v39
	global_store_dword v[74:75], v22, off offset:192
	s_waitcnt lgkmcnt(0)
	v_mul_f32_e32 v23, v23, v30
	v_exp_f32_e32 v24, v24
	v_mul_f32_e32 v23, v39, v23
	v_cvt_pk_bf16_f32 v23, v31, v23
	v_add_f32_e32 v31, v106, v32
	v_mul_f32_e32 v31, 0xbfb8aa3b, v31
	v_exp_f32_e32 v31, v31
	ds_read_b32 v30, v101 offset:5088
	v_add_f32_e32 v24, 1.0, v24
	v_rcp_f32_e32 v24, v24
	v_add_f32_e32 v31, 1.0, v31
	v_rcp_f32_e32 v31, v31
	global_store_dword v[74:75], v23, off offset:1216
	s_waitcnt lgkmcnt(0)
	v_mul_f32_e32 v24, v24, v30
	v_add_f32_e32 v0, v0, v25
	v_mul_f32_e32 v31, 0xc1000000, v31
	v_mul_f32_e32 v31, v27, v31
	v_mul_f32_e32 v32, 0x3fb8aa3b, v31
	v_exp_f32_e32 v32, v32
	v_mul_f32_e32 v0, 0xbfb8aa3b, v0
	v_exp_f32_e32 v0, v0
	v_lshlrev_b32_e32 v26, 16, v28
	v_sub_f32_e32 v39, 1.0, v32
	v_add_f32_e32 v32, 1.0, v32
	v_mul_f32_e32 v32, v39, v32
	v_sqrt_f32_e32 v32, v32
	v_add_f32_e32 v0, 1.0, v0
	v_lshlrev_b32_e32 v29, 16, v34
	v_lshlrev_b32_e32 v35, 16, v36
	v_mul_f32_e32 v24, v32, v24
	v_cvt_pk_bf16_f32 v24, v31, v24
	v_add_f32_e32 v31, v106, v33
	v_mul_f32_e32 v31, 0xbfb8aa3b, v31
	v_exp_f32_e32 v31, v31
	ds_read_b32 v30, v101 offset:5360
	v_rcp_f32_e32 v0, v0
	v_mul_f32_e32 v26, 0x3fb8aa3b, v26
	v_add_f32_e32 v31, 1.0, v31
	v_rcp_f32_e32 v31, v31
	v_mul_f32_e32 v29, 0x3fb8aa3b, v29
	v_mul_f32_e32 v35, 0x3fb8aa3b, v35
	v_exp_f32_e32 v26, v26
	v_mul_f32_e32 v25, 0xc1000000, v31
	v_mul_f32_e32 v25, v27, v25
	v_mul_f32_e32 v27, 0x3fb8aa3b, v25
	v_exp_f32_e32 v27, v27
	v_exp_f32_e32 v29, v29
	v_exp_f32_e32 v35, v35
	s_waitcnt lgkmcnt(0)
	v_mul_f32_e32 v0, v0, v30
	v_sub_f32_e32 v31, 1.0, v27
	v_add_f32_e32 v27, 1.0, v27
	v_mul_f32_e32 v27, v31, v27
	v_sqrt_f32_e32 v27, v27
	v_and_b32_e32 v28, 0xffff0000, v28
	v_and_b32_e32 v34, 0xffff0000, v34
	v_and_b32_e32 v36, 0xffff0000, v36
	v_and_b32_e32 v37, 0xffff0000, v38
	v_mul_f32_e32 v0, v27, v0
	s_and_b64 vcc, exec, s[38:39]
	global_store_dword v[74:75], v24, off offset:2240
	v_cvt_pk_bf16_f32 v0, v25, v0
	global_store_dword v[74:75], v0, off offset:3264
	s_cbranch_vccnz .LBB0_772
	v_fma_f32 v25, v35, v37, v36
	v_fma_f32 v25, v29, v25, v34
	v_fma_f32 v25, v26, v25, v28
	s_mov_b64 s[4:5], 0

; #define LAS __attribute__((address_space(3)))
; #define MFMA16(a, b, c) __builtin_amdgcn_mfma_f32_16x16x32_bf16((a), (b), (c), 0, 0, 0)
; #define S5_LOAD(rb_) do { _Pragma("unroll") for (int j_ = 0; j_ < 3; ++j_) { const int p_ = tid + j_ * 512, rr_ = p_ / 96, kc_ = p_ % 96, r_ = (rb_) * 16 + rr_; \
;         st[j_] = kc_ < 64 ? ld8(P + (size_t)(tokbase_of(r_) + (kc_ >> 1)) * INP + OFF_S5 + g * 16 + (kc_ & 1) * 8) : ld8(S5H + ((size_t)r_ * 16 + g) * 256 + (kc_ - 64) * 8); } } while (0)
; #define S5_STORE(buf_) do { _Pragma("unroll") for (int j_ = 0; j_ < 3; ++j_) { const int p_ = tid + j_ * 512, rr_ = p_ / 96, kc_ = p_ % 96; *(LAS u32x4*)(lds + (buf_) * BUF + rr_ * RST + kc_ * 16) = st[j_]; } } while (0)
; #define S5_LOAD(rb_) do { _Pragma("unroll") for (int j_ = 0; j_ < 2; ++j_) { const int p_ = tid + j_ * 512, rr_ = p_ >> 6, kc_ = p_ & 63, r_ = (rb_) * 16 + rr_; \
;         st[j_] = ld8(P + (size_t)(tokbase_of(r_) + (kc_ >> 1)) * INP + OFF_S5 + g * 16 + (kc_ & 1) * 8); } } while (0)
; #define S5_STORE(buf_) do { _Pragma("unroll") for (int j_ = 0; j_ < 2; ++j_) { const int p_ = tid + j_ * 512, rr_ = p_ >> 6, kc_ = p_ & 63; *(LAS u32x4*)(lds + (buf_) * BUF + rr_ * RST + kc_ * 16) = st[j_]; } } while (0)
; __device__ __forceinline__ void s5_pass1_block(LAS unsigned char* lds, int bt, int l, const bf16_t* P, const bf16_t* WEND, float* S5S) {
;     ...
;     for (int i = 0; i < 3; ++i) {
;         const int rb = rg * 3 + i;
;         S5_STORE(i & 1);
;         __syncthreads();
;         if (i < 2) S5_LOAD(rb + 1);
;         const LAS unsigned char* ab = lds + (i & 1) * BUF + fr * RST + fq * 16;
;         f32x4 acc0 = (f32x4){0.f, 0.f, 0.f, 0.f}, acc1 = acc0;
; #pragma unroll
;         for (int ks = 0; ks < 16; ++ks) { const bf16x8 af = *(const LAS bf16x8*)(ab + ks * 64); acc0 = MFMA16(af, bw[0][ks], acc0); acc1 = MFMA16(af, bw[1][ks], acc1); }
; #pragma unroll
;         for (int q = 0; q < 4; ++q) { float* o = S5S + ((size_t)(rb * 16 + fq * 4 + q) * 16 + g) * 256 + wave * 32 + fr; o[0] = acc0[q]; o[16] = acc1[q]; }
;     }
.LBB0_784:
	s_or_b64 exec, exec, s[20:21]
	ds_read_b128 v[156:159], v0 offset:16640
	ds_read_b128 v[164:167], v0 offset:16704
	v_add_u32_e32 v140, v139, v149
	v_mov_b64_e32 v[138:139], s[36:37]
	v_mad_i64_i32 v[138:139], s[20:21], v140, s84, v[138:139]
	v_lshl_add_u64 v[138:139], s[40:41], 1, v[138:139]
	v_mov_b32_e32 v145, v1
	v_lshl_add_u64 v[138:139], v[138:139], 0, v[144:145]
	s_waitcnt lgkmcnt(0)
	v_mfma_f32_16x16x32_bf16 v[160:163], v[156:159], v[118:121], 0
	global_load_dwordx4 v[138:141], v[138:139], off offset:320
	v_subrev_u32_e32 v144, 19, v146
	v_ashrrev_i32_e32 v145, 31, v144
	v_mfma_f32_16x16x32_bf16 v[156:159], v[156:159], v[130:133], 0
	v_lshlrev_b64 v[144:145], 14, v[144:145]
	v_lshl_add_u64 v[144:145], v[142:143], 0, v[144:145]
	s_mul_i32 s14, s74, 48
	v_mfma_f32_16x16x32_bf16 v[160:163], v[164:167], v[106:109], v[160:163]
	s_add_i32 s18, s18, s74
	s_add_i32 s7, s7, s14
	s_cmpk_lt_i32 s18, 0xc0
	v_mfma_f32_16x16x32_bf16 v[156:159], v[164:167], v[126:129], v[156:159]
	ds_read_b128 v[164:167], v0 offset:16768
	s_waitcnt lgkmcnt(0)
	v_mfma_f32_16x16x32_bf16 v[160:163], v[164:167], v[102:105], v[160:163]
	v_mfma_f32_16x16x32_bf16 v[156:159], v[164:167], v[122:125], v[156:159]
	ds_read_b128 v[164:167], v0 offset:16832
	s_waitcnt lgkmcnt(0)
	v_mfma_f32_16x16x32_bf16 v[160:163], v[164:167], v[90:93], v[160:163]
	v_mfma_f32_16x16x32_bf16 v[156:159], v[164:167], v[114:117], v[156:159]
	ds_read_b128 v[164:167], v0 offset:16896
	s_waitcnt lgkmcnt(0)
	v_mfma_f32_16x16x32_bf16 v[160:163], v[164:167], v[86:89], v[160:163]
	v_mfma_f32_16x16x32_bf16 v[156:159], v[164:167], v[110:113], v[156:159]
	ds_read_b128 v[164:167], v0 offset:16960
	s_waitcnt lgkmcnt(0)
	v_mfma_f32_16x16x32_bf16 v[160:163], v[164:167], v[74:77], v[160:163]
	v_mfma_f32_16x16x32_bf16 v[156:159], v[164:167], v[98:101], v[156:159]
	ds_read_b128 v[164:167], v0 offset:17024
	s_waitcnt lgkmcnt(0)
	v_mfma_f32_16x16x32_bf16 v[160:163], v[164:167], v[70:73], v[160:163]
	v_mfma_f32_16x16x32_bf16 v[156:159], v[164:167], v[94:97], v[156:159]
	ds_read_b128 v[164:167], v0 offset:17088
	s_waitcnt lgkmcnt(0)
	v_mfma_f32_16x16x32_bf16 v[160:163], v[164:167], v[58:61], v[160:163]
	v_mfma_f32_16x16x32_bf16 v[156:159], v[164:167], v[82:85], v[156:159]
	ds_read_b128 v[164:167], v0 offset:17152
	s_waitcnt lgkmcnt(0)
	v_mfma_f32_16x16x32_bf16 v[160:163], v[164:167], v[54:57], v[160:163]
	v_mfma_f32_16x16x32_bf16 v[156:159], v[164:167], v[78:81], v[156:159]
	ds_read_b128 v[164:167], v0 offset:17216
	s_waitcnt lgkmcnt(0)
	v_mfma_f32_16x16x32_bf16 v[160:163], v[164:167], v[42:45], v[160:163]
	v_mfma_f32_16x16x32_bf16 v[156:159], v[164:167], v[66:69], v[156:159]
	ds_read_b128 v[164:167], v0 offset:17280
	s_waitcnt lgkmcnt(0)
	v_mfma_f32_16x16x32_bf16 v[160:163], v[164:167], v[38:41], v[160:163]
	v_mfma_f32_16x16x32_bf16 v[156:159], v[164:167], v[62:65], v[156:159]
	ds_read_b128 v[164:167], v0 offset:17344
	s_waitcnt lgkmcnt(0)
	v_mfma_f32_16x16x32_bf16 v[160:163], v[164:167], v[26:29], v[160:163]
	v_mfma_f32_16x16x32_bf16 v[156:159], v[164:167], v[50:53], v[156:159]
	ds_read_b128 v[164:167], v0 offset:17408
	s_waitcnt lgkmcnt(0)
	v_mfma_f32_16x16x32_bf16 v[160:163], v[164:167], v[22:25], v[160:163]
	v_mfma_f32_16x16x32_bf16 v[156:159], v[164:167], v[46:49], v[156:159]
	ds_read_b128 v[164:167], v0 offset:17472
	s_waitcnt lgkmcnt(0)
	v_mfma_f32_16x16x32_bf16 v[160:163], v[164:167], v[14:17], v[160:163]
	v_mfma_f32_16x16x32_bf16 v[156:159], v[164:167], v[34:37], v[156:159]
	ds_read_b128 v[164:167], v0 offset:17536
	s_waitcnt lgkmcnt(0)
	v_mfma_f32_16x16x32_bf16 v[160:163], v[164:167], v[6:9], v[160:163]
	v_mfma_f32_16x16x32_bf16 v[156:159], v[164:167], v[30:33], v[156:159]
	ds_read_b128 v[164:167], v0 offset:17600
	s_waitcnt lgkmcnt(0)
	v_mfma_f32_16x16x32_bf16 v[160:163], v[164:167], v[2:5], v[160:163]
	v_mfma_f32_16x16x32_bf16 v[156:159], v[164:167], v[18:21], v[156:159]
	s_nop 6
	global_store_dword v[144:145], v160, off
	global_store_dword v[144:145], v156, off offset:64
	v_subrev_u32_e32 v144, 18, v146
	v_ashrrev_i32_e32 v145, 31, v144
	v_lshlrev_b64 v[144:145], 14, v[144:145]
	v_lshl_add_u64 v[144:145], v[142:143], 0, v[144:145]
	global_store_dword v[144:145], v161, off
	global_store_dword v[144:145], v157, off offset:64
	v_subrev_u32_e32 v144, 17, v146
	v_ashrrev_i32_e32 v145, 31, v144
	v_lshlrev_b64 v[144:145], 14, v[144:145]
	v_lshl_add_u64 v[144:145], v[142:143], 0, v[144:145]
	global_store_dword v[144:145], v162, off
	global_store_dword v[144:145], v158, off offset:64
	v_add_u32_e32 v144, -16, v146
	v_ashrrev_i32_e32 v145, 31, v144
	v_lshlrev_b64 v[144:145], 14, v[144:145]
	v_lshl_add_u64 v[144:145], v[142:143], 0, v[144:145]
	global_store_dword v[144:145], v163, off
	global_store_dword v[144:145], v159, off offset:64
	s_waitcnt vmcnt(0)
	ds_write_b128 v147, v[134:137]
	ds_write_b128 v148, v[138:141]
	s_waitcnt lgkmcnt(0)
	s_barrier
; #define LAS __attribute__((address_space(3)))
; #define MFMA16(a, b, c) __builtin_amdgcn_mfma_f32_16x16x32_bf16((a), (b), (c), 0, 0, 0)
; #define S5_LOAD(rb_) do { _Pragma("unroll") for (int j_ = 0; j_ < 3; ++j_) { const int p_ = tid + j_ * 512, rr_ = p_ / 96, kc_ = p_ % 96, r_ = (rb_) * 16 + rr_; \
;         st[j_] = kc_ < 64 ? ld8(P + (size_t)(tokbase_of(r_) + (kc_ >> 1)) * INP + OFF_S5 + g * 16 + (kc_ & 1) * 8) : ld8(S5H + ((size_t)r_ * 16 + g) * 256 + (kc_ - 64) * 8); } } while (0)
; #define S5_STORE(buf_) do { _Pragma("unroll") for (int j_ = 0; j_ < 3; ++j_) { const int p_ = tid + j_ * 512, rr_ = p_ / 96, kc_ = p_ % 96; *(LAS u32x4*)(lds + (buf_) * BUF + rr_ * RST + kc_ * 16) = st[j_]; } } while (0)
; #define S5_LOAD(rb_) do { _Pragma("unroll") for (int j_ = 0; j_ < 2; ++j_) { const int p_ = tid + j_ * 512, rr_ = p_ >> 6, kc_ = p_ & 63, r_ = (rb_) * 16 + rr_; \
;         st[j_] = ld8(P + (size_t)(tokbase_of(r_) + (kc_ >> 1)) * INP + OFF_S5 + g * 16 + (kc_ & 1) * 8); } } while (0)
; #define S5_STORE(buf_) do { _Pragma("unroll") for (int j_ = 0; j_ < 2; ++j_) { const int p_ = tid + j_ * 512, rr_ = p_ >> 6, kc_ = p_ & 63; *(LAS u32x4*)(lds + (buf_) * BUF + rr_ * RST + kc_ * 16) = st[j_]; } } while (0)
; __device__ __forceinline__ void s5_pass1_block(LAS unsigned char* lds, int bt, int l, const bf16_t* P, const bf16_t* WEND, float* S5S) {
;     ...
;     for (int i = 0; i < 3; ++i) {
;         const int rb = rg * 3 + i;
;         S5_STORE(i & 1);
;         __syncthreads();
;         if (i < 2) S5_LOAD(rb + 1);
;         const LAS unsigned char* ab = lds + (i & 1) * BUF + fr * RST + fq * 16;
;         f32x4 acc0 = (f32x4){0.f, 0.f, 0.f, 0.f}, acc1 = acc0;
; #pragma unroll
;         for (int ks = 0; ks < 16; ++ks) { const bf16x8 af = *(const LAS bf16x8*)(ab + ks * 64); acc0 = MFMA16(af, bw[0][ks], acc0); acc1 = MFMA16(af, bw[1][ks], acc1); }
; #pragma unroll
;         for (int q = 0; q < 4; ++q) { float* o = S5S + ((size_t)(rb * 16 + fq * 4 + q) * 16 + g) * 256 + wave * 32 + fr; o[0] = acc0[q]; o[16] = acc1[q]; }
;     }
	ds_read_b128 v[134:137], v0
	s_waitcnt lgkmcnt(0)
	v_mfma_f32_16x16x32_bf16 v[118:121], v[134:137], v[118:121], 0
	v_ashrrev_i32_e32 v147, 31, v146
	v_mfma_f32_16x16x32_bf16 v[130:133], v[134:137], v[130:133], 0
	ds_read_b128 v[134:137], v0 offset:64
	s_waitcnt lgkmcnt(0)
	v_mfma_f32_16x16x32_bf16 v[106:109], v[134:137], v[106:109], v[118:121]
	v_mfma_f32_16x16x32_bf16 v[118:121], v[134:137], v[126:129], v[130:133]
	ds_read_b128 v[126:129], v0 offset:128
	s_waitcnt lgkmcnt(0)
	v_mfma_f32_16x16x32_bf16 v[102:105], v[126:129], v[102:105], v[106:109]
	v_mfma_f32_16x16x32_bf16 v[106:109], v[126:129], v[122:125], v[118:121]
	s_nop 3
	ds_read_b128 v[118:121], v0 offset:192
	s_waitcnt lgkmcnt(0)
	v_mfma_f32_16x16x32_bf16 v[90:93], v[118:121], v[90:93], v[102:105]
	v_mfma_f32_16x16x32_bf16 v[102:105], v[118:121], v[114:117], v[106:109]
	s_nop 2
	ds_read_b128 v[106:109], v0 offset:256
	s_waitcnt lgkmcnt(0)
	v_mfma_f32_16x16x32_bf16 v[86:89], v[106:109], v[86:89], v[90:93]
	v_mfma_f32_16x16x32_bf16 v[90:93], v[106:109], v[110:113], v[102:105]
	s_nop 2
	ds_read_b128 v[102:105], v0 offset:320
	s_waitcnt lgkmcnt(0)
	v_mfma_f32_16x16x32_bf16 v[74:77], v[102:105], v[74:77], v[86:89]
	v_mfma_f32_16x16x32_bf16 v[86:89], v[102:105], v[98:101], v[90:93]
	s_nop 2
	ds_read_b128 v[90:93], v0 offset:384
	s_waitcnt lgkmcnt(0)
	v_mfma_f32_16x16x32_bf16 v[70:73], v[90:93], v[70:73], v[74:77]
	v_mfma_f32_16x16x32_bf16 v[74:77], v[90:93], v[94:97], v[86:89]
	s_nop 2
	ds_read_b128 v[86:89], v0 offset:448
	s_waitcnt lgkmcnt(0)
	v_mfma_f32_16x16x32_bf16 v[58:61], v[86:89], v[58:61], v[70:73]
	v_mfma_f32_16x16x32_bf16 v[70:73], v[86:89], v[82:85], v[74:77]
	s_nop 2
	ds_read_b128 v[74:77], v0 offset:512
	s_waitcnt lgkmcnt(0)
	v_mfma_f32_16x16x32_bf16 v[54:57], v[74:77], v[54:57], v[58:61]
	v_mfma_f32_16x16x32_bf16 v[58:61], v[74:77], v[78:81], v[70:73]
	s_nop 2
	ds_read_b128 v[70:73], v0 offset:576
	s_waitcnt lgkmcnt(0)
	v_mfma_f32_16x16x32_bf16 v[42:45], v[70:73], v[42:45], v[54:57]
	v_mfma_f32_16x16x32_bf16 v[54:57], v[70:73], v[66:69], v[58:61]
	s_nop 2
	ds_read_b128 v[58:61], v0 offset:640
	s_waitcnt lgkmcnt(0)
	v_mfma_f32_16x16x32_bf16 v[38:41], v[58:61], v[38:41], v[42:45]
	v_mfma_f32_16x16x32_bf16 v[42:45], v[58:61], v[62:65], v[54:57]
	s_nop 2
	ds_read_b128 v[54:57], v0 offset:704
	s_waitcnt lgkmcnt(0)
	v_mfma_f32_16x16x32_bf16 v[26:29], v[54:57], v[26:29], v[38:41]
	v_mfma_f32_16x16x32_bf16 v[38:41], v[54:57], v[50:53], v[42:45]
	s_nop 2
	ds_read_b128 v[42:45], v0 offset:768
	s_waitcnt lgkmcnt(0)
	v_mfma_f32_16x16x32_bf16 v[22:25], v[42:45], v[22:25], v[26:29]
	v_mfma_f32_16x16x32_bf16 v[26:29], v[42:45], v[46:49], v[38:41]
	s_nop 2
	ds_read_b128 v[38:41], v0 offset:832
	s_waitcnt lgkmcnt(0)
	v_mfma_f32_16x16x32_bf16 v[14:17], v[38:41], v[14:17], v[22:25]
	v_mfma_f32_16x16x32_bf16 v[22:25], v[38:41], v[34:37], v[26:29]
	s_nop 2
	ds_read_b128 v[26:29], v0 offset:896
	s_waitcnt lgkmcnt(0)
	v_mfma_f32_16x16x32_bf16 v[6:9], v[26:29], v[6:9], v[14:17]
	v_mfma_f32_16x16x32_bf16 v[14:17], v[26:29], v[30:33], v[22:25]
	s_nop 2
	ds_read_b128 v[22:25], v0 offset:960
	s_waitcnt lgkmcnt(0)
	v_mfma_f32_16x16x32_bf16 v[2:5], v[22:25], v[2:5], v[6:9]
	v_mfma_f32_16x16x32_bf16 v[6:9], v[22:25], v[18:21], v[14:17]
	s_nop 2
	v_add_u32_e32 v14, -3, v146
	v_ashrrev_i32_e32 v15, 31, v14
	v_lshlrev_b64 v[14:15], 14, v[14:15]
	v_lshl_add_u64 v[14:15], v[142:143], 0, v[14:15]
	global_store_dword v[14:15], v2, off
	global_store_dword v[14:15], v6, off offset:64
	v_add_u32_e32 v14, -2, v146
	v_ashrrev_i32_e32 v15, 31, v14
	v_lshlrev_b64 v[14:15], 14, v[14:15]
	v_lshl_add_u64 v[14:15], v[142:143], 0, v[14:15]
	v_add_u32_e32 v2, -1, v146
	global_store_dword v[14:15], v3, off
	global_store_dword v[14:15], v7, off offset:64
	v_ashrrev_i32_e32 v3, 31, v2
	v_lshlrev_b64 v[2:3], 14, v[2:3]
	v_lshl_add_u64 v[2:3], v[142:143], 0, v[2:3]
	global_store_dword v[2:3], v4, off
	global_store_dword v[2:3], v8, off offset:64
	v_lshlrev_b64 v[2:3], 14, v[146:147]
	v_lshl_add_u64 v[2:3], v[142:143], 0, v[2:3]
	global_store_dword v[2:3], v5, off
	global_store_dword v[2:3], v9, off offset:64
	s_waitcnt lgkmcnt(0)
	s_barrier
	s_cbranch_scc0 .LBB0_809
.LBB0_785:
	s_mul_hi_i32 s15, s18, 0x2aaaaaab
	s_lshr_b32 s19, s15, 31
	s_ashr_i32 s15, s15, 1
	s_add_i32 s20, s15, s19
	v_readlane_b32 s15, v254, 35
	v_mov_b32 v140, v194
	s_add_i32 s22, s20, s15
	v_readfirstlane_b32 s14, v140
	s_ashr_i32 s23, s22, 31
	s_ashr_i32 s14, s14, 1
	v_and_b32_e32 v138, 15, v140
	s_lshl_b64 s[24:25], s[22:23], 8
	s_and_b32 s22, s14, 0xffffffe0
	v_or_b32_e32 v18, s24, v138
	s_or_b32 s24, s22, 16
	v_bfe_u32 v139, v140, 4, 2
	v_mov_b32_e32 v19, s25
	s_ashr_i32 s23, s22, 31
	s_ashr_i32 s25, s24, 31
	s_waitcnt lgkmcnt(0)
; #define S5_LOAD(rb_) do { _Pragma("unroll") for (int j_ = 0; j_ < 3; ++j_) { const int p_ = tid + j_ * 512, rr_ = p_ / 96, kc_ = p_ % 96, r_ = (rb_) * 16 + rr_; \
;         st[j_] = kc_ < 64 ? ld8(P + (size_t)(tokbase_of(r_) + (kc_ >> 1)) * INP + OFF_S5 + g * 16 + (kc_ & 1) * 8) : ld8(S5H + ((size_t)r_ * 16 + g) * 256 + (kc_ - 64) * 8); } } while (0)
; #define S5_STORE(buf_) do { _Pragma("unroll") for (int j_ = 0; j_ < 3; ++j_) { const int p_ = tid + j_ * 512, rr_ = p_ / 96, kc_ = p_ % 96; *(LAS u32x4*)(lds + (buf_) * BUF + rr_ * RST + kc_ * 16) = st[j_]; } } while (0)
; #define S5_LOAD(rb_) do { _Pragma("unroll") for (int j_ = 0; j_ < 2; ++j_) { const int p_ = tid + j_ * 512, rr_ = p_ >> 6, kc_ = p_ & 63, r_ = (rb_) * 16 + rr_; \
;         st[j_] = ld8(P + (size_t)(tokbase_of(r_) + (kc_ >> 1)) * INP + OFF_S5 + g * 16 + (kc_ & 1) * 8); } } while (0)
; #define S5_STORE(buf_) do { _Pragma("unroll") for (int j_ = 0; j_ < 2; ++j_) { const int p_ = tid + j_ * 512, rr_ = p_ >> 6, kc_ = p_ & 63; *(LAS u32x4*)(lds + (buf_) * BUF + rr_ * RST + kc_ * 16) = st[j_]; } } while (0)
; __device__ __forceinline__ void s5_pass1_block(LAS unsigned char* lds, int bt, int l, const bf16_t* P, const bf16_t* WEND, float* S5S) {
;     ...
;     bf16x8 bw[2][16];
; #pragma unroll
;     for (int c2 = 0; c2 < 2; ++c2) { const bf16_t* bp = WEND + ((size_t)(l * 16 + g) * 256 + (wave * 2 + c2) * 16 + fr) * 512 + fq * 8;
; #pragma unroll
;         for (int ks = 0; ks < 16; ++ks) bw[c2][ks] = asfrag(ld8(bp + ks * 32)); }
;     u32x4 st[2];
;     ...
;     __syncthreads();
;     S5_LOAD(rg * 3);
;     for (int i = 0; i < 3; ++i) {
;         const int rb = rg * 3 + i;
;         S5_STORE(i & 1);
	v_lshlrev_b32_e32 v0, 4, v139
	v_lshl_add_u64 v[2:3], v[18:19], 0, s[22:23]
	v_lshl_add_u64 v[18:19], v[18:19], 0, s[24:25]
	v_lshl_add_u64 v[20:21], s[38:39], 0, v[0:1]
	v_lshlrev_b64 v[2:3], 10, v[2:3]
	v_lshlrev_b64 v[18:19], 10, v[18:19]
	v_lshl_add_u64 v[2:3], v[20:21], 0, v[2:3]
	v_lshl_add_u64 v[18:19], v[20:21], 0, v[18:19]
	global_load_dwordx4 v[118:121], v[2:3], off
	global_load_dwordx4 v[106:109], v[2:3], off offset:64
	global_load_dwordx4 v[102:105], v[2:3], off offset:128
	global_load_dwordx4 v[90:93], v[2:3], off offset:192
	global_load_dwordx4 v[86:89], v[2:3], off offset:256
	global_load_dwordx4 v[74:77], v[2:3], off offset:320
	global_load_dwordx4 v[70:73], v[2:3], off offset:384
	global_load_dwordx4 v[58:61], v[2:3], off offset:448
	global_load_dwordx4 v[54:57], v[2:3], off offset:512
	global_load_dwordx4 v[42:45], v[2:3], off offset:576
	global_load_dwordx4 v[38:41], v[2:3], off offset:640
	global_load_dwordx4 v[26:29], v[2:3], off offset:704
	global_load_dwordx4 v[22:25], v[2:3], off offset:768
	global_load_dwordx4 v[14:17], v[2:3], off offset:832
	global_load_dwordx4 v[6:9], v[2:3], off offset:896
	s_nop 0
	global_load_dwordx4 v[2:5], v[2:3], off offset:960
	s_nop 0
	global_load_dwordx4 v[130:133], v[18:19], off
	global_load_dwordx4 v[126:129], v[18:19], off offset:64
	global_load_dwordx4 v[122:125], v[18:19], off offset:128
	global_load_dwordx4 v[114:117], v[18:19], off offset:192
	global_load_dwordx4 v[110:113], v[18:19], off offset:256
	global_load_dwordx4 v[98:101], v[18:19], off offset:320
	global_load_dwordx4 v[94:97], v[18:19], off offset:384
	global_load_dwordx4 v[82:85], v[18:19], off offset:448
	global_load_dwordx4 v[78:81], v[18:19], off offset:512
	global_load_dwordx4 v[66:69], v[18:19], off offset:576
	global_load_dwordx4 v[62:65], v[18:19], off offset:640
	global_load_dwordx4 v[50:53], v[18:19], off offset:704
	global_load_dwordx4 v[46:49], v[18:19], off offset:768
	global_load_dwordx4 v[34:37], v[18:19], off offset:832
	global_load_dwordx4 v[30:33], v[18:19], off offset:896
	s_nop 0
	global_load_dwordx4 v[18:21], v[18:19], off offset:960
	v_ashrrev_i32_e32 v141, 6, v140
	s_mul_i32 s19, s20, 0x240
	v_subrev_u32_e32 v134, s19, v141
	v_add_u32_e32 v156, s7, v134
	v_subrev_u32_e32 v134, 35, v156
	v_mul_hi_i32 v134, v134, s94
	v_lshrrev_b32_e32 v135, 31, v134
	v_ashrrev_i32_e32 v134, 4, v134
	v_add_u32_e32 v135, v134, v135
	v_mul_lo_u32 v134, v135, s85
	v_sub_u32_e32 v134, v141, v134
	v_subrev_u32_e32 v134, s19, v134
	v_add_u32_e32 v134, s7, v134
	v_subrev_u32_e32 v134, 35, v134
	v_cmp_lt_i32_e32 vcc, 7, v134
	v_lshlrev_b32_e32 v136, 5, v134
	s_waitcnt lgkmcnt(0)
	s_barrier
	s_and_saveexec_b64 s[24:25], vcc
	s_xor_b64 s[24:25], exec, s[24:25]
	v_lshlrev_b32_e32 v134, 11, v135
	v_add3_u32 v134, v136, v134, s95
	s_andn2_saveexec_b64 s[24:25], s[24:25]
	v_lshlrev_b32_e32 v134, 8, v135
	v_add3_u32 v134, v134, v136, s0
	s_or_b64 exec, exec, s[24:25]
	v_bfe_u32 v149, v140, 1, 5
	v_lshlrev_b32_e32 v135, 3, v140
	s_lshl_b32 s40, s20, 4
	v_and_b32_e32 v136, 8, v135
	v_add_u32_e32 v137, v134, v149
	v_mov_b64_e32 v[134:135], s[36:37]
	s_ashr_i32 s41, s40, 31
	v_mad_i64_i32 v[134:135], s[24:25], v137, s84, v[134:135]
	v_lshl_add_u64 v[134:135], s[40:41], 1, v[134:135]
	v_lshlrev_b32_e32 v144, 1, v136
	v_mov_b32_e32 v145, v1
	v_lshl_add_u64 v[134:135], v[134:135], 0, v[144:145]
	global_load_dwordx4 v[134:137], v[134:135], off offset:320
	v_add_u32_e32 v142, 0x200, v140
	v_ashrrev_i32_e32 v142, 6, v142
	v_subrev_u32_e32 v143, s19, v142
	v_add_u32_e32 v157, s7, v143
	v_subrev_u32_e32 v143, 35, v157
	v_mul_hi_i32 v143, v143, s94
	v_lshrrev_b32_e32 v145, 31, v143
	v_ashrrev_i32_e32 v143, 4, v143
	v_add_u32_e32 v143, v143, v145
	v_mul_lo_u32 v145, v143, s85
	v_sub_u32_e32 v145, v142, v145
	v_subrev_u32_e32 v145, s19, v145
	v_add_u32_e32 v145, s7, v145
	v_subrev_u32_e32 v145, 35, v145
	v_cmp_lt_i32_e32 vcc, 7, v145
	v_lshlrev_b32_e32 v146, 5, v145
	s_and_saveexec_b64 s[24:25], vcc
	s_xor_b64 s[24:25], exec, s[24:25]
	v_lshlrev_b32_e32 v143, 11, v143
	v_add3_u32 v145, v146, v143, s95
	s_andn2_saveexec_b64 s[24:25], s[24:25]
	v_lshlrev_b32_e32 v143, 8, v143
	v_add3_u32 v145, v143, v146, s0
	s_or_b64 exec, exec, s[24:25]
	v_add_u32_e32 v143, v145, v149
	v_mov_b64_e32 v[146:147], s[36:37]
	v_mad_i64_i32 v[146:147], s[24:25], v143, s84, v[146:147]
	v_lshl_add_u64 v[146:147], s[40:41], 1, v[146:147]
	v_mov_b32_e32 v145, v1
	v_lshl_add_u64 v[146:147], v[146:147], 0, v[144:145]
	global_load_dwordx4 v[158:161], v[146:147], off offset:320
	v_lshlrev_b32_e32 v140, 4, v140
	v_and_b32_e32 v140, 0x3f0, v140
	s_movk_i32 s14, 0x410
	v_add_u32_e32 v140, 0, v140
	v_mul_lo_u32 v141, v141, s14
	v_add_u32_e32 v147, v140, v141
	s_waitcnt vmcnt(0) lgkmcnt(0)
	ds_write_b128 v147, v[134:137]
	v_mul_lo_u32 v134, v142, s14
	v_subrev_u32_e32 v135, 19, v156
	v_add_u32_e32 v148, v140, v134
	v_mul_hi_i32 v134, v135, s94
	v_lshrrev_b32_e32 v136, 31, v134
	v_ashrrev_i32_e32 v134, 4, v134
	v_add_u32_e32 v134, v134, v136
	v_mul_lo_u32 v136, v134, s85
	v_sub_u32_e32 v135, v135, v136
	v_cmp_lt_i32_e32 vcc, 7, v135
	v_lshlrev_b32_e32 v136, 5, v135
	ds_write_b128 v148, v[158:161]
	s_waitcnt lgkmcnt(0)
	s_barrier
; #define LAS __attribute__((address_space(3)))
; #define MFMA16(a, b, c) __builtin_amdgcn_mfma_f32_16x16x32_bf16((a), (b), (c), 0, 0, 0)
; #define S5_LOAD(rb_) do { _Pragma("unroll") for (int j_ = 0; j_ < 3; ++j_) { const int p_ = tid + j_ * 512, rr_ = p_ / 96, kc_ = p_ % 96, r_ = (rb_) * 16 + rr_; \
;         st[j_] = kc_ < 64 ? ld8(P + (size_t)(tokbase_of(r_) + (kc_ >> 1)) * INP + OFF_S5 + g * 16 + (kc_ & 1) * 8) : ld8(S5H + ((size_t)r_ * 16 + g) * 256 + (kc_ - 64) * 8); } } while (0)
; #define S5_STORE(buf_) do { _Pragma("unroll") for (int j_ = 0; j_ < 3; ++j_) { const int p_ = tid + j_ * 512, rr_ = p_ / 96, kc_ = p_ % 96; *(LAS u32x4*)(lds + (buf_) * BUF + rr_ * RST + kc_ * 16) = st[j_]; } } while (0)
; #define S5_LOAD(rb_) do { _Pragma("unroll") for (int j_ = 0; j_ < 2; ++j_) { const int p_ = tid + j_ * 512, rr_ = p_ >> 6, kc_ = p_ & 63, r_ = (rb_) * 16 + rr_; \
;         st[j_] = ld8(P + (size_t)(tokbase_of(r_) + (kc_ >> 1)) * INP + OFF_S5 + g * 16 + (kc_ & 1) * 8); } } while (0)
; #define S5_STORE(buf_) do { _Pragma("unroll") for (int j_ = 0; j_ < 2; ++j_) { const int p_ = tid + j_ * 512, rr_ = p_ >> 6, kc_ = p_ & 63; *(LAS u32x4*)(lds + (buf_) * BUF + rr_ * RST + kc_ * 16) = st[j_]; } } while (0)
; __device__ __forceinline__ void s5_pass1_block(LAS unsigned char* lds, int bt, int l, const bf16_t* P, const bf16_t* WEND, float* S5S) {
;     ...
;     __syncthreads();
;     S5_LOAD(rg * 3);
;     for (int i = 0; i < 3; ++i) {
;         const int rb = rg * 3 + i;
;         S5_STORE(i & 1);
;         __syncthreads();
;         if (i < 2) S5_LOAD(rb + 1);
;         const LAS unsigned char* ab = lds + (i & 1) * BUF + fr * RST + fq * 16;
;         f32x4 acc0 = (f32x4){0.f, 0.f, 0.f, 0.f}, acc1 = acc0;
; #pragma unroll
;         for (int ks = 0; ks < 16; ++ks) { const bf16x8 af = *(const LAS bf16x8*)(ab + ks * 64); acc0 = MFMA16(af, bw[0][ks], acc0); acc1 = MFMA16(af, bw[1][ks], acc1); }
; #pragma unroll
;         for (int q = 0; q < 4; ++q) { float* o = S5S + ((size_t)(rb * 16 + fq * 4 + q) * 16 + g) * 256 + wave * 32 + fr; o[0] = acc0[q]; o[16] = acc1[q]; }
;     }
	s_and_saveexec_b64 s[24:25], vcc
	s_xor_b64 s[24:25], exec, s[24:25]
	v_lshlrev_b32_e32 v134, 11, v134
	v_add3_u32 v135, v136, v134, s95
	s_andn2_saveexec_b64 s[24:25], s[24:25]
	v_lshlrev_b32_e32 v134, 8, v134
	v_add3_u32 v135, v134, v136, s0
	s_or_b64 exec, exec, s[24:25]
	v_add_u32_e32 v136, v135, v149
	v_mov_b64_e32 v[134:135], s[36:37]
	v_mad_i64_i32 v[134:135], s[24:25], v136, s84, v[134:135]
	v_lshl_add_u64 v[134:135], s[40:41], 1, v[134:135]
	v_mov_b32_e32 v145, v1
	v_lshl_add_u64 v[134:135], v[134:135], 0, v[144:145]
	global_load_dwordx4 v[134:137], v[134:135], off offset:320
	v_subrev_u32_e32 v140, 19, v157
	v_mul_hi_i32 v141, v140, s94
	v_lshrrev_b32_e32 v142, 31, v141
	v_ashrrev_i32_e32 v141, 4, v141
	v_add_u32_e32 v141, v141, v142
	v_mul_lo_u32 v142, v141, s85
	v_sub_u32_e32 v140, v140, v142
	v_cmp_lt_i32_e32 vcc, 7, v140
	v_lshlrev_b32_e32 v142, 5, v140
	s_and_saveexec_b64 s[24:25], vcc
	s_xor_b64 s[24:25], exec, s[24:25]
	v_lshlrev_b32_e32 v140, 11, v141
	v_add3_u32 v140, v142, v140, s95
	s_andn2_saveexec_b64 s[24:25], s[24:25]
	v_lshlrev_b32_e32 v140, 8, v141
	v_add3_u32 v140, v140, v142, s0
	s_or_b64 exec, exec, s[24:25]
	v_mul_u32_u24_e32 v141, 0x410, v138
	v_add_u32_e32 v146, 0, v141
	v_add_u32_e32 v0, v146, v0
	ds_read_b128 v[158:161], v0
	ds_read_b128 v[166:169], v0 offset:64
	s_ashr_i32 s21, s20, 31
	s_lshl_b64 s[20:21], s[20:21], 10
	s_add_u32 s14, s1, s20
	s_addc_u32 s15, s6, s21
	s_lshl_b64 s[20:21], s[22:23], 2
	s_add_u32 s20, s14, s20
	v_lshlrev_b32_e32 v170, 2, v139
	s_waitcnt lgkmcnt(0)
	v_mfma_f32_16x16x32_bf16 v[162:165], v[158:161], v[118:121], 0
	s_addc_u32 s21, s15, s21
	v_lshlrev_b32_e32 v138, 2, v138
	v_mov_b32_e32 v139, v1
	v_mfma_f32_16x16x32_bf16 v[158:161], v[158:161], v[130:133], 0
	v_lshl_add_u64 v[142:143], s[20:21], 0, v[138:139]
	v_add_u32_e32 v140, v140, v149
	v_mov_b64_e32 v[138:139], s[36:37]
	v_mfma_f32_16x16x32_bf16 v[162:165], v[166:169], v[106:109], v[162:165]
	v_mad_i64_i32 v[138:139], s[20:21], v140, s84, v[138:139]
	v_lshl_add_u64 v[138:139], s[40:41], 1, v[138:139]
	v_mfma_f32_16x16x32_bf16 v[158:161], v[166:169], v[126:129], v[158:161]
	ds_read_b128 v[166:169], v0 offset:128
	v_mov_b32_e32 v145, v1
	v_lshl_add_u64 v[138:139], v[138:139], 0, v[144:145]
	s_waitcnt lgkmcnt(0)
	v_mfma_f32_16x16x32_bf16 v[162:165], v[166:169], v[102:105], v[162:165]
	global_load_dwordx4 v[138:141], v[138:139], off offset:320
	v_subrev_u32_e32 v145, s19, v170
	v_add_u32_e32 v146, s7, v145
	v_mfma_f32_16x16x32_bf16 v[158:161], v[166:169], v[122:125], v[158:161]
	ds_read_b128 v[166:169], v0 offset:192
	s_waitcnt lgkmcnt(0)
	v_mfma_f32_16x16x32_bf16 v[162:165], v[166:169], v[90:93], v[162:165]
	v_mfma_f32_16x16x32_bf16 v[158:161], v[166:169], v[114:117], v[158:161]
	ds_read_b128 v[166:169], v0 offset:256
	s_waitcnt lgkmcnt(0)
	v_mfma_f32_16x16x32_bf16 v[162:165], v[166:169], v[86:89], v[162:165]
	v_mfma_f32_16x16x32_bf16 v[158:161], v[166:169], v[110:113], v[158:161]
	ds_read_b128 v[166:169], v0 offset:320
	s_waitcnt lgkmcnt(0)
	v_mfma_f32_16x16x32_bf16 v[162:165], v[166:169], v[74:77], v[162:165]
	v_mfma_f32_16x16x32_bf16 v[158:161], v[166:169], v[98:101], v[158:161]
	ds_read_b128 v[166:169], v0 offset:384
	s_waitcnt lgkmcnt(0)
	v_mfma_f32_16x16x32_bf16 v[162:165], v[166:169], v[70:73], v[162:165]
	v_mfma_f32_16x16x32_bf16 v[158:161], v[166:169], v[94:97], v[158:161]
	ds_read_b128 v[166:169], v0 offset:448
	s_waitcnt lgkmcnt(0)
	v_mfma_f32_16x16x32_bf16 v[162:165], v[166:169], v[58:61], v[162:165]
	v_mfma_f32_16x16x32_bf16 v[158:161], v[166:169], v[82:85], v[158:161]
	ds_read_b128 v[166:169], v0 offset:512
	s_waitcnt lgkmcnt(0)
	v_mfma_f32_16x16x32_bf16 v[162:165], v[166:169], v[54:57], v[162:165]
	v_mfma_f32_16x16x32_bf16 v[158:161], v[166:169], v[78:81], v[158:161]
	ds_read_b128 v[166:169], v0 offset:576
	s_waitcnt lgkmcnt(0)
	v_mfma_f32_16x16x32_bf16 v[162:165], v[166:169], v[42:45], v[162:165]
	v_mfma_f32_16x16x32_bf16 v[158:161], v[166:169], v[66:69], v[158:161]
	ds_read_b128 v[166:169], v0 offset:640
	s_waitcnt lgkmcnt(0)
	v_mfma_f32_16x16x32_bf16 v[162:165], v[166:169], v[38:41], v[162:165]
	v_mfma_f32_16x16x32_bf16 v[158:161], v[166:169], v[62:65], v[158:161]
	ds_read_b128 v[166:169], v0 offset:704
	s_waitcnt lgkmcnt(0)
	v_mfma_f32_16x16x32_bf16 v[162:165], v[166:169], v[26:29], v[162:165]
	v_mfma_f32_16x16x32_bf16 v[158:161], v[166:169], v[50:53], v[158:161]
	ds_read_b128 v[166:169], v0 offset:768
	s_waitcnt lgkmcnt(0)
	v_mfma_f32_16x16x32_bf16 v[162:165], v[166:169], v[22:25], v[162:165]
	v_mfma_f32_16x16x32_bf16 v[158:161], v[166:169], v[46:49], v[158:161]
	ds_read_b128 v[166:169], v0 offset:832
	s_waitcnt lgkmcnt(0)
	v_mfma_f32_16x16x32_bf16 v[162:165], v[166:169], v[14:17], v[162:165]
	v_mfma_f32_16x16x32_bf16 v[158:161], v[166:169], v[34:37], v[158:161]
	ds_read_b128 v[166:169], v0 offset:896
	s_waitcnt lgkmcnt(0)
	v_mfma_f32_16x16x32_bf16 v[162:165], v[166:169], v[6:9], v[162:165]
	v_mfma_f32_16x16x32_bf16 v[158:161], v[166:169], v[30:33], v[158:161]
	ds_read_b128 v[166:169], v0 offset:960
	s_waitcnt lgkmcnt(0)
	v_mfma_f32_16x16x32_bf16 v[162:165], v[166:169], v[2:5], v[162:165]
	v_mfma_f32_16x16x32_bf16 v[158:161], v[166:169], v[18:21], v[158:161]
	v_subrev_u32_e32 v166, 35, v146
	v_ashrrev_i32_e32 v167, 31, v166
	v_lshlrev_b64 v[166:167], 14, v[166:167]
	v_lshl_add_u64 v[166:167], v[142:143], 0, v[166:167]
	s_nop 2
	global_store_dword v[166:167], v162, off
	global_store_dword v[166:167], v158, off offset:64
	v_subrev_u32_e32 v166, 34, v146
	v_ashrrev_i32_e32 v167, 31, v166
	v_lshlrev_b64 v[166:167], 14, v[166:167]
	v_lshl_add_u64 v[166:167], v[142:143], 0, v[166:167]
	v_subrev_u32_e32 v158, 33, v146
	global_store_dword v[166:167], v163, off
	global_store_dword v[166:167], v159, off offset:64
	v_ashrrev_i32_e32 v159, 31, v158
	v_lshlrev_b64 v[158:159], 14, v[158:159]
	v_lshl_add_u64 v[158:159], v[142:143], 0, v[158:159]
	global_store_dword v[158:159], v164, off
	global_store_dword v[158:159], v160, off offset:64
	v_subrev_u32_e32 v158, 32, v146
	v_ashrrev_i32_e32 v159, 31, v158
	v_lshlrev_b64 v[158:159], 14, v[158:159]
	v_lshl_add_u64 v[158:159], v[142:143], 0, v[158:159]
	global_store_dword v[158:159], v165, off
	global_store_dword v[158:159], v161, off offset:64
	s_waitcnt vmcnt(0)
	ds_write_b128 v147, v[134:137] offset:16640
	ds_write_b128 v148, v[138:141] offset:16640
	v_add_u32_e32 v135, -3, v156
	v_mul_hi_i32 v134, v135, s94
	v_lshrrev_b32_e32 v136, 31, v134
	v_ashrrev_i32_e32 v134, 4, v134
	v_add_u32_e32 v134, v134, v136
	v_mul_lo_u32 v136, v134, s85
	v_sub_u32_e32 v135, v135, v136
	v_cmp_lt_i32_e32 vcc, 7, v135
	v_lshlrev_b32_e32 v136, 5, v135
	s_waitcnt lgkmcnt(0)
	s_barrier
	s_and_saveexec_b64 s[20:21], vcc
	s_xor_b64 s[20:21], exec, s[20:21]
	v_lshlrev_b32_e32 v134, 11, v134
	v_add3_u32 v135, v136, v134, s95
	s_andn2_saveexec_b64 s[20:21], s[20:21]
	v_lshlrev_b32_e32 v134, 8, v134
	v_add3_u32 v135, v134, v136, s0
	s_or_b64 exec, exec, s[20:21]
	v_add_u32_e32 v136, v135, v149
	v_mov_b64_e32 v[134:135], s[36:37]
	v_mad_i64_i32 v[134:135], s[20:21], v136, s84, v[134:135]
	v_lshl_add_u64 v[134:135], s[40:41], 1, v[134:135]
	v_mov_b32_e32 v145, v1
	v_lshl_add_u64 v[134:135], v[134:135], 0, v[144:145]
	global_load_dwordx4 v[134:137], v[134:135], off offset:320
	v_add_u32_e32 v139, -3, v157
	v_mul_hi_i32 v138, v139, s94
	v_lshrrev_b32_e32 v140, 31, v138
	v_ashrrev_i32_e32 v138, 4, v138
	v_add_u32_e32 v138, v138, v140
	v_mul_lo_u32 v140, v138, s85
	v_sub_u32_e32 v139, v139, v140
	v_cmp_lt_i32_e32 vcc, 7, v139
	v_lshlrev_b32_e32 v140, 5, v139
	s_and_saveexec_b64 s[20:21], vcc
	s_xor_b64 s[20:21], exec, s[20:21]
	v_lshlrev_b32_e32 v138, 11, v138
	v_add3_u32 v139, v140, v138, s95
	s_andn2_saveexec_b64 s[20:21], s[20:21]
	s_cbranch_execz .LBB0_784
	v_lshlrev_b32_e32 v138, 8, v138
	v_add3_u32 v139, v138, v140, s0
	s_branch .LBB0_784

; #define LAS __attribute__((address_space(3)))
; #define MFMA16(a, b, c) __builtin_amdgcn_mfma_f32_16x16x32_bf16((a), (b), (c), 0, 0, 0)
; #define S5_LOAD(rb_) do { _Pragma("unroll") for (int j_ = 0; j_ < 3; ++j_) { const int p_ = tid + j_ * 512, rr_ = p_ / 96, kc_ = p_ % 96, r_ = (rb_) * 16 + rr_; \
;         st[j_] = kc_ < 64 ? ld8(P + (size_t)(tokbase_of(r_) + (kc_ >> 1)) * INP + OFF_S5 + g * 16 + (kc_ & 1) * 8) : ld8(S5H + ((size_t)r_ * 16 + g) * 256 + (kc_ - 64) * 8); } } while (0)
; #define S5_STORE(buf_) do { _Pragma("unroll") for (int j_ = 0; j_ < 3; ++j_) { const int p_ = tid + j_ * 512, rr_ = p_ / 96, kc_ = p_ % 96; *(LAS u32x4*)(lds + (buf_) * BUF + rr_ * RST + kc_ * 16) = st[j_]; } } while (0)
; #define S5_LOAD(rb_) do { _Pragma("unroll") for (int j_ = 0; j_ < 2; ++j_) { const int p_ = tid + j_ * 512, rr_ = p_ >> 6, kc_ = p_ & 63, r_ = (rb_) * 16 + rr_; \
;         st[j_] = ld8(P + (size_t)(tokbase_of(r_) + (kc_ >> 1)) * INP + OFF_S5 + g * 16 + (kc_ & 1) * 8); } } while (0)
; #define S5_STORE(buf_) do { _Pragma("unroll") for (int j_ = 0; j_ < 2; ++j_) { const int p_ = tid + j_ * 512, rr_ = p_ >> 6, kc_ = p_ & 63; *(LAS u32x4*)(lds + (buf_) * BUF + rr_ * RST + kc_ * 16) = st[j_]; } } while (0)
; __device__ __forceinline__ void s5_pass1_block(LAS unsigned char* lds, int bt, int l, const bf16_t* P, const bf16_t* WEND, float* S5S) {
;     ...
;     for (int i = 0; i < 3; ++i) {
;         const int rb = rg * 3 + i;
;         S5_STORE(i & 1);
;         __syncthreads();
;         if (i < 2) S5_LOAD(rb + 1);
;         const LAS unsigned char* ab = lds + (i & 1) * BUF + fr * RST + fq * 16;
;         f32x4 acc0 = (f32x4){0.f, 0.f, 0.f, 0.f}, acc1 = acc0;
; #pragma unroll
;         for (int ks = 0; ks < 16; ++ks) { const bf16x8 af = *(const LAS bf16x8*)(ab + ks * 64); acc0 = MFMA16(af, bw[0][ks], acc0); acc1 = MFMA16(af, bw[1][ks], acc1); }
; #pragma unroll
;         for (int q = 0; q < 4; ++q) { float* o = S5S + ((size_t)(rb * 16 + fq * 4 + q) * 16 + g) * 256 + wave * 32 + fr; o[0] = acc0[q]; o[16] = acc1[q]; }
;     }
.LBB0_813:
	s_or_b64 exec, exec, s[20:21]
	ds_read_b128 v[156:159], v0 offset:16640
	ds_read_b128 v[164:167], v0 offset:16704
	v_add_u32_e32 v140, v139, v149
	v_mov_b64_e32 v[138:139], s[36:37]
	v_mad_i64_i32 v[138:139], s[20:21], v140, s84, v[138:139]
	v_lshl_add_u64 v[138:139], s[4:5], 1, v[138:139]
	v_mov_b32_e32 v145, v1
	v_lshl_add_u64 v[138:139], v[138:139], 0, v[144:145]
	s_waitcnt lgkmcnt(0)
	v_mfma_f32_16x16x32_bf16 v[160:163], v[156:159], v[118:121], 0
	global_load_dwordx4 v[138:141], v[138:139], off offset:320
	v_subrev_u32_e32 v144, 19, v146
	v_ashrrev_i32_e32 v145, 31, v144
	v_mfma_f32_16x16x32_bf16 v[156:159], v[156:159], v[130:133], 0
	v_lshlrev_b64 v[144:145], 14, v[144:145]
	v_lshl_add_u64 v[144:145], v[142:143], 0, v[144:145]
	v_readlane_b32 s4, v254, 38
	v_mfma_f32_16x16x32_bf16 v[160:163], v[164:167], v[106:109], v[160:163]
	s_add_i32 s18, s18, s4
	s_mul_i32 s4, s4, 48
	s_add_i32 s7, s7, s4
	v_mfma_f32_16x16x32_bf16 v[156:159], v[164:167], v[126:129], v[156:159]
	ds_read_b128 v[164:167], v0 offset:16768
	s_cmpk_gt_i32 s18, 0xbf
	s_waitcnt lgkmcnt(0)
	v_mfma_f32_16x16x32_bf16 v[160:163], v[164:167], v[102:105], v[160:163]
	v_mfma_f32_16x16x32_bf16 v[156:159], v[164:167], v[122:125], v[156:159]
	ds_read_b128 v[164:167], v0 offset:16832
	s_waitcnt lgkmcnt(0)
	v_mfma_f32_16x16x32_bf16 v[160:163], v[164:167], v[90:93], v[160:163]
	v_mfma_f32_16x16x32_bf16 v[156:159], v[164:167], v[114:117], v[156:159]
	ds_read_b128 v[164:167], v0 offset:16896
	s_waitcnt lgkmcnt(0)
	v_mfma_f32_16x16x32_bf16 v[160:163], v[164:167], v[86:89], v[160:163]
	v_mfma_f32_16x16x32_bf16 v[156:159], v[164:167], v[110:113], v[156:159]
	ds_read_b128 v[164:167], v0 offset:16960
	s_waitcnt lgkmcnt(0)
	v_mfma_f32_16x16x32_bf16 v[160:163], v[164:167], v[74:77], v[160:163]
	v_mfma_f32_16x16x32_bf16 v[156:159], v[164:167], v[98:101], v[156:159]
	ds_read_b128 v[164:167], v0 offset:17024
	s_waitcnt lgkmcnt(0)
	v_mfma_f32_16x16x32_bf16 v[160:163], v[164:167], v[70:73], v[160:163]
	v_mfma_f32_16x16x32_bf16 v[156:159], v[164:167], v[94:97], v[156:159]
	ds_read_b128 v[164:167], v0 offset:17088
	s_waitcnt lgkmcnt(0)
	v_mfma_f32_16x16x32_bf16 v[160:163], v[164:167], v[58:61], v[160:163]
	v_mfma_f32_16x16x32_bf16 v[156:159], v[164:167], v[82:85], v[156:159]
	ds_read_b128 v[164:167], v0 offset:17152
	s_waitcnt lgkmcnt(0)
	v_mfma_f32_16x16x32_bf16 v[160:163], v[164:167], v[54:57], v[160:163]
	v_mfma_f32_16x16x32_bf16 v[156:159], v[164:167], v[78:81], v[156:159]
	ds_read_b128 v[164:167], v0 offset:17216
	s_waitcnt lgkmcnt(0)
	v_mfma_f32_16x16x32_bf16 v[160:163], v[164:167], v[42:45], v[160:163]
	v_mfma_f32_16x16x32_bf16 v[156:159], v[164:167], v[66:69], v[156:159]
	ds_read_b128 v[164:167], v0 offset:17280
	s_waitcnt lgkmcnt(0)
	v_mfma_f32_16x16x32_bf16 v[160:163], v[164:167], v[38:41], v[160:163]
	v_mfma_f32_16x16x32_bf16 v[156:159], v[164:167], v[62:65], v[156:159]
	ds_read_b128 v[164:167], v0 offset:17344
	s_waitcnt lgkmcnt(0)
	v_mfma_f32_16x16x32_bf16 v[160:163], v[164:167], v[26:29], v[160:163]
	v_mfma_f32_16x16x32_bf16 v[156:159], v[164:167], v[50:53], v[156:159]
	ds_read_b128 v[164:167], v0 offset:17408
	s_waitcnt lgkmcnt(0)
	v_mfma_f32_16x16x32_bf16 v[160:163], v[164:167], v[22:25], v[160:163]
	v_mfma_f32_16x16x32_bf16 v[156:159], v[164:167], v[46:49], v[156:159]
	ds_read_b128 v[164:167], v0 offset:17472
	s_waitcnt lgkmcnt(0)
	v_mfma_f32_16x16x32_bf16 v[160:163], v[164:167], v[14:17], v[160:163]
	v_mfma_f32_16x16x32_bf16 v[156:159], v[164:167], v[34:37], v[156:159]
	ds_read_b128 v[164:167], v0 offset:17536
	s_waitcnt lgkmcnt(0)
	v_mfma_f32_16x16x32_bf16 v[160:163], v[164:167], v[6:9], v[160:163]
	v_mfma_f32_16x16x32_bf16 v[156:159], v[164:167], v[30:33], v[156:159]
	ds_read_b128 v[164:167], v0 offset:17600
	s_waitcnt lgkmcnt(0)
	v_mfma_f32_16x16x32_bf16 v[160:163], v[164:167], v[2:5], v[160:163]
	v_mfma_f32_16x16x32_bf16 v[156:159], v[164:167], v[18:21], v[156:159]
	s_nop 6
	global_store_dword v[144:145], v160, off
	global_store_dword v[144:145], v156, off offset:64
	v_subrev_u32_e32 v144, 18, v146
	v_ashrrev_i32_e32 v145, 31, v144
	v_lshlrev_b64 v[144:145], 14, v[144:145]
	v_lshl_add_u64 v[144:145], v[142:143], 0, v[144:145]
	global_store_dword v[144:145], v161, off
	global_store_dword v[144:145], v157, off offset:64
	v_subrev_u32_e32 v144, 17, v146
	v_ashrrev_i32_e32 v145, 31, v144
	v_lshlrev_b64 v[144:145], 14, v[144:145]
	v_lshl_add_u64 v[144:145], v[142:143], 0, v[144:145]
	global_store_dword v[144:145], v162, off
	global_store_dword v[144:145], v158, off offset:64
	v_add_u32_e32 v144, -16, v146
	v_ashrrev_i32_e32 v145, 31, v144
	v_lshlrev_b64 v[144:145], 14, v[144:145]
	v_lshl_add_u64 v[144:145], v[142:143], 0, v[144:145]
	global_store_dword v[144:145], v163, off
	global_store_dword v[144:145], v159, off offset:64
	s_waitcnt vmcnt(0)
	ds_write_b128 v147, v[134:137]
	ds_write_b128 v148, v[138:141]
	s_waitcnt lgkmcnt(0)
	s_barrier
; #define LAS __attribute__((address_space(3)))
; #define MFMA16(a, b, c) __builtin_amdgcn_mfma_f32_16x16x32_bf16((a), (b), (c), 0, 0, 0)
; #define S5_LOAD(rb_) do { _Pragma("unroll") for (int j_ = 0; j_ < 3; ++j_) { const int p_ = tid + j_ * 512, rr_ = p_ / 96, kc_ = p_ % 96, r_ = (rb_) * 16 + rr_; \
;         st[j_] = kc_ < 64 ? ld8(P + (size_t)(tokbase_of(r_) + (kc_ >> 1)) * INP + OFF_S5 + g * 16 + (kc_ & 1) * 8) : ld8(S5H + ((size_t)r_ * 16 + g) * 256 + (kc_ - 64) * 8); } } while (0)
; #define S5_STORE(buf_) do { _Pragma("unroll") for (int j_ = 0; j_ < 3; ++j_) { const int p_ = tid + j_ * 512, rr_ = p_ / 96, kc_ = p_ % 96; *(LAS u32x4*)(lds + (buf_) * BUF + rr_ * RST + kc_ * 16) = st[j_]; } } while (0)
; #define S5_LOAD(rb_) do { _Pragma("unroll") for (int j_ = 0; j_ < 2; ++j_) { const int p_ = tid + j_ * 512, rr_ = p_ >> 6, kc_ = p_ & 63, r_ = (rb_) * 16 + rr_; \
;         st[j_] = ld8(P + (size_t)(tokbase_of(r_) + (kc_ >> 1)) * INP + OFF_S5 + g * 16 + (kc_ & 1) * 8); } } while (0)
; #define S5_STORE(buf_) do { _Pragma("unroll") for (int j_ = 0; j_ < 2; ++j_) { const int p_ = tid + j_ * 512, rr_ = p_ >> 6, kc_ = p_ & 63; *(LAS u32x4*)(lds + (buf_) * BUF + rr_ * RST + kc_ * 16) = st[j_]; } } while (0)
; __device__ __forceinline__ void s5_pass1_block(LAS unsigned char* lds, int bt, int l, const bf16_t* P, const bf16_t* WEND, float* S5S) {
;     ...
;     for (int i = 0; i < 3; ++i) {
;         const int rb = rg * 3 + i;
;         S5_STORE(i & 1);
;         __syncthreads();
;         if (i < 2) S5_LOAD(rb + 1);
;         const LAS unsigned char* ab = lds + (i & 1) * BUF + fr * RST + fq * 16;
;         f32x4 acc0 = (f32x4){0.f, 0.f, 0.f, 0.f}, acc1 = acc0;
; #pragma unroll
;         for (int ks = 0; ks < 16; ++ks) { const bf16x8 af = *(const LAS bf16x8*)(ab + ks * 64); acc0 = MFMA16(af, bw[0][ks], acc0); acc1 = MFMA16(af, bw[1][ks], acc1); }
; #pragma unroll
;         for (int q = 0; q < 4; ++q) { float* o = S5S + ((size_t)(rb * 16 + fq * 4 + q) * 16 + g) * 256 + wave * 32 + fr; o[0] = acc0[q]; o[16] = acc1[q]; }
;     }
	ds_read_b128 v[134:137], v0
	s_waitcnt lgkmcnt(0)
	v_mfma_f32_16x16x32_bf16 v[118:121], v[134:137], v[118:121], 0
	v_ashrrev_i32_e32 v147, 31, v146
	v_mfma_f32_16x16x32_bf16 v[130:133], v[134:137], v[130:133], 0
	ds_read_b128 v[134:137], v0 offset:64
	s_waitcnt lgkmcnt(0)
	v_mfma_f32_16x16x32_bf16 v[106:109], v[134:137], v[106:109], v[118:121]
	v_mfma_f32_16x16x32_bf16 v[118:121], v[134:137], v[126:129], v[130:133]
	ds_read_b128 v[126:129], v0 offset:128
	s_waitcnt lgkmcnt(0)
	v_mfma_f32_16x16x32_bf16 v[102:105], v[126:129], v[102:105], v[106:109]
	v_mfma_f32_16x16x32_bf16 v[106:109], v[126:129], v[122:125], v[118:121]
	s_nop 3
	ds_read_b128 v[118:121], v0 offset:192
	s_waitcnt lgkmcnt(0)
	v_mfma_f32_16x16x32_bf16 v[90:93], v[118:121], v[90:93], v[102:105]
	v_mfma_f32_16x16x32_bf16 v[102:105], v[118:121], v[114:117], v[106:109]
	s_nop 2
	ds_read_b128 v[106:109], v0 offset:256
	s_waitcnt lgkmcnt(0)
	v_mfma_f32_16x16x32_bf16 v[86:89], v[106:109], v[86:89], v[90:93]
	v_mfma_f32_16x16x32_bf16 v[90:93], v[106:109], v[110:113], v[102:105]
	s_nop 2
	ds_read_b128 v[102:105], v0 offset:320
	s_waitcnt lgkmcnt(0)
	v_mfma_f32_16x16x32_bf16 v[74:77], v[102:105], v[74:77], v[86:89]
	v_mfma_f32_16x16x32_bf16 v[86:89], v[102:105], v[98:101], v[90:93]
	s_nop 2
	ds_read_b128 v[90:93], v0 offset:384
	s_waitcnt lgkmcnt(0)
	v_mfma_f32_16x16x32_bf16 v[70:73], v[90:93], v[70:73], v[74:77]
	v_mfma_f32_16x16x32_bf16 v[74:77], v[90:93], v[94:97], v[86:89]
	s_nop 2
	ds_read_b128 v[86:89], v0 offset:448
	s_waitcnt lgkmcnt(0)
	v_mfma_f32_16x16x32_bf16 v[58:61], v[86:89], v[58:61], v[70:73]
	v_mfma_f32_16x16x32_bf16 v[70:73], v[86:89], v[82:85], v[74:77]
	s_nop 2
	ds_read_b128 v[74:77], v0 offset:512
	s_waitcnt lgkmcnt(0)
	v_mfma_f32_16x16x32_bf16 v[54:57], v[74:77], v[54:57], v[58:61]
	v_mfma_f32_16x16x32_bf16 v[58:61], v[74:77], v[78:81], v[70:73]
	s_nop 2
	ds_read_b128 v[70:73], v0 offset:576
	s_waitcnt lgkmcnt(0)
	v_mfma_f32_16x16x32_bf16 v[42:45], v[70:73], v[42:45], v[54:57]
	v_mfma_f32_16x16x32_bf16 v[54:57], v[70:73], v[66:69], v[58:61]
	s_nop 2
	ds_read_b128 v[58:61], v0 offset:640
	s_waitcnt lgkmcnt(0)
	v_mfma_f32_16x16x32_bf16 v[38:41], v[58:61], v[38:41], v[42:45]
	v_mfma_f32_16x16x32_bf16 v[42:45], v[58:61], v[62:65], v[54:57]
	s_nop 2
	ds_read_b128 v[54:57], v0 offset:704
	s_waitcnt lgkmcnt(0)
	v_mfma_f32_16x16x32_bf16 v[26:29], v[54:57], v[26:29], v[38:41]
	v_mfma_f32_16x16x32_bf16 v[38:41], v[54:57], v[50:53], v[42:45]
	s_nop 2
	ds_read_b128 v[42:45], v0 offset:768
	s_waitcnt lgkmcnt(0)
	v_mfma_f32_16x16x32_bf16 v[22:25], v[42:45], v[22:25], v[26:29]
	v_mfma_f32_16x16x32_bf16 v[26:29], v[42:45], v[46:49], v[38:41]
	s_nop 2
	ds_read_b128 v[38:41], v0 offset:832
	s_waitcnt lgkmcnt(0)
	v_mfma_f32_16x16x32_bf16 v[14:17], v[38:41], v[14:17], v[22:25]
	v_mfma_f32_16x16x32_bf16 v[22:25], v[38:41], v[34:37], v[26:29]
	s_nop 2
	ds_read_b128 v[26:29], v0 offset:896
	s_waitcnt lgkmcnt(0)
	v_mfma_f32_16x16x32_bf16 v[6:9], v[26:29], v[6:9], v[14:17]
	v_mfma_f32_16x16x32_bf16 v[14:17], v[26:29], v[30:33], v[22:25]
	s_nop 2
	ds_read_b128 v[22:25], v0 offset:960
	s_waitcnt lgkmcnt(0)
	v_mfma_f32_16x16x32_bf16 v[2:5], v[22:25], v[2:5], v[6:9]
	v_mfma_f32_16x16x32_bf16 v[6:9], v[22:25], v[18:21], v[14:17]
	s_nop 2
	v_add_u32_e32 v14, -3, v146
	v_ashrrev_i32_e32 v15, 31, v14
	v_lshlrev_b64 v[14:15], 14, v[14:15]
	v_lshl_add_u64 v[14:15], v[142:143], 0, v[14:15]
	global_store_dword v[14:15], v2, off
	global_store_dword v[14:15], v6, off offset:64
	v_add_u32_e32 v14, -2, v146
	v_ashrrev_i32_e32 v15, 31, v14
	v_lshlrev_b64 v[14:15], 14, v[14:15]
	v_lshl_add_u64 v[14:15], v[142:143], 0, v[14:15]
	v_add_u32_e32 v2, -1, v146
	global_store_dword v[14:15], v3, off
	global_store_dword v[14:15], v7, off offset:64
	v_ashrrev_i32_e32 v3, 31, v2
	v_lshlrev_b64 v[2:3], 14, v[2:3]
	v_lshl_add_u64 v[2:3], v[142:143], 0, v[2:3]
	global_store_dword v[2:3], v4, off
	global_store_dword v[2:3], v8, off offset:64
	v_lshlrev_b64 v[2:3], 14, v[146:147]
	v_lshl_add_u64 v[2:3], v[142:143], 0, v[2:3]
	global_store_dword v[2:3], v5, off
	global_store_dword v[2:3], v9, off offset:64
	s_waitcnt lgkmcnt(0)
	s_barrier
	s_cbranch_scc1 .LBB0_838
.LBB0_814:
	s_mul_hi_i32 s4, s18, 0x2aaaaaab
	s_lshr_b32 s5, s4, 31
	s_ashr_i32 s4, s4, 1
	s_add_i32 s20, s4, s5
	v_readlane_b32 s4, v254, 35
	v_mov_b32 v140, v194
	s_add_i32 s4, s20, s4
	v_readfirstlane_b32 s14, v140
	s_ashr_i32 s5, s4, 31
	s_ashr_i32 s14, s14, 1
	v_and_b32_e32 v138, 15, v140
	s_lshl_b64 s[4:5], s[4:5], 8
	s_and_b32 s22, s14, 0xffffffe0
	v_or_b32_e32 v18, s4, v138
	s_or_b32 s4, s22, 16
	v_bfe_u32 v139, v140, 4, 2
	v_mov_b32_e32 v19, s5
	s_ashr_i32 s23, s22, 31
	s_ashr_i32 s5, s4, 31
	s_waitcnt lgkmcnt(0)
; #define S5_LOAD(rb_) do { _Pragma("unroll") for (int j_ = 0; j_ < 3; ++j_) { const int p_ = tid + j_ * 512, rr_ = p_ / 96, kc_ = p_ % 96, r_ = (rb_) * 16 + rr_; \
;         st[j_] = kc_ < 64 ? ld8(P + (size_t)(tokbase_of(r_) + (kc_ >> 1)) * INP + OFF_S5 + g * 16 + (kc_ & 1) * 8) : ld8(S5H + ((size_t)r_ * 16 + g) * 256 + (kc_ - 64) * 8); } } while (0)
; #define S5_STORE(buf_) do { _Pragma("unroll") for (int j_ = 0; j_ < 3; ++j_) { const int p_ = tid + j_ * 512, rr_ = p_ / 96, kc_ = p_ % 96; *(LAS u32x4*)(lds + (buf_) * BUF + rr_ * RST + kc_ * 16) = st[j_]; } } while (0)
; #define S5_LOAD(rb_) do { _Pragma("unroll") for (int j_ = 0; j_ < 2; ++j_) { const int p_ = tid + j_ * 512, rr_ = p_ >> 6, kc_ = p_ & 63, r_ = (rb_) * 16 + rr_; \
;         st[j_] = ld8(P + (size_t)(tokbase_of(r_) + (kc_ >> 1)) * INP + OFF_S5 + g * 16 + (kc_ & 1) * 8); } } while (0)
; #define S5_STORE(buf_) do { _Pragma("unroll") for (int j_ = 0; j_ < 2; ++j_) { const int p_ = tid + j_ * 512, rr_ = p_ >> 6, kc_ = p_ & 63; *(LAS u32x4*)(lds + (buf_) * BUF + rr_ * RST + kc_ * 16) = st[j_]; } } while (0)
; __device__ __forceinline__ void s5_pass1_block(LAS unsigned char* lds, int bt, int l, const bf16_t* P, const bf16_t* WEND, float* S5S) {
;     ...
;     bf16x8 bw[2][16];
; #pragma unroll
;     for (int c2 = 0; c2 < 2; ++c2) { const bf16_t* bp = WEND + ((size_t)(l * 16 + g) * 256 + (wave * 2 + c2) * 16 + fr) * 512 + fq * 8;
; #pragma unroll
;         for (int ks = 0; ks < 16; ++ks) bw[c2][ks] = asfrag(ld8(bp + ks * 32)); }
;     u32x4 st[2];
;     ...
;     __syncthreads();
;     S5_LOAD(rg * 3);
;     for (int i = 0; i < 3; ++i) {
;         const int rb = rg * 3 + i;
;         S5_STORE(i & 1);
	v_lshlrev_b32_e32 v0, 4, v139
	v_lshl_add_u64 v[2:3], v[18:19], 0, s[22:23]
	v_lshl_add_u64 v[18:19], v[18:19], 0, s[4:5]
	v_lshl_add_u64 v[20:21], s[38:39], 0, v[0:1]
	v_lshlrev_b64 v[2:3], 10, v[2:3]
	v_lshlrev_b64 v[18:19], 10, v[18:19]
	v_lshl_add_u64 v[2:3], v[20:21], 0, v[2:3]
	v_lshl_add_u64 v[18:19], v[20:21], 0, v[18:19]
	global_load_dwordx4 v[118:121], v[2:3], off
	global_load_dwordx4 v[106:109], v[2:3], off offset:64
	global_load_dwordx4 v[102:105], v[2:3], off offset:128
	global_load_dwordx4 v[90:93], v[2:3], off offset:192
	global_load_dwordx4 v[86:89], v[2:3], off offset:256
	global_load_dwordx4 v[74:77], v[2:3], off offset:320
	global_load_dwordx4 v[70:73], v[2:3], off offset:384
	global_load_dwordx4 v[58:61], v[2:3], off offset:448
	global_load_dwordx4 v[54:57], v[2:3], off offset:512
	global_load_dwordx4 v[42:45], v[2:3], off offset:576
	global_load_dwordx4 v[38:41], v[2:3], off offset:640
	global_load_dwordx4 v[26:29], v[2:3], off offset:704
	global_load_dwordx4 v[22:25], v[2:3], off offset:768
	global_load_dwordx4 v[14:17], v[2:3], off offset:832
	global_load_dwordx4 v[6:9], v[2:3], off offset:896
	s_nop 0
	global_load_dwordx4 v[2:5], v[2:3], off offset:960
	s_nop 0
	global_load_dwordx4 v[130:133], v[18:19], off
	global_load_dwordx4 v[126:129], v[18:19], off offset:64
	global_load_dwordx4 v[122:125], v[18:19], off offset:128
	global_load_dwordx4 v[114:117], v[18:19], off offset:192
	global_load_dwordx4 v[110:113], v[18:19], off offset:256
	global_load_dwordx4 v[98:101], v[18:19], off offset:320
	global_load_dwordx4 v[94:97], v[18:19], off offset:384
	global_load_dwordx4 v[82:85], v[18:19], off offset:448
	global_load_dwordx4 v[78:81], v[18:19], off offset:512
	global_load_dwordx4 v[66:69], v[18:19], off offset:576
	global_load_dwordx4 v[62:65], v[18:19], off offset:640
	global_load_dwordx4 v[50:53], v[18:19], off offset:704
	global_load_dwordx4 v[46:49], v[18:19], off offset:768
	global_load_dwordx4 v[34:37], v[18:19], off offset:832
	global_load_dwordx4 v[30:33], v[18:19], off offset:896
	s_nop 0
	global_load_dwordx4 v[18:21], v[18:19], off offset:960
	v_ashrrev_i32_e32 v141, 6, v140
	s_mul_i32 s19, s20, 0x240
	v_subrev_u32_e32 v134, s19, v141
	v_add_u32_e32 v156, s7, v134
	v_subrev_u32_e32 v134, 35, v156
	v_mul_hi_i32 v134, v134, s94
	v_lshrrev_b32_e32 v135, 31, v134
	v_ashrrev_i32_e32 v134, 4, v134
	v_add_u32_e32 v135, v134, v135
	v_mul_lo_u32 v134, v135, s85
	v_sub_u32_e32 v134, v141, v134
	v_subrev_u32_e32 v134, s19, v134
	v_add_u32_e32 v134, s7, v134
	v_subrev_u32_e32 v134, 35, v134
	v_cmp_lt_i32_e32 vcc, 7, v134
	v_lshlrev_b32_e32 v136, 5, v134
	s_waitcnt lgkmcnt(0)
	s_barrier
	s_and_saveexec_b64 s[4:5], vcc
	s_xor_b64 s[4:5], exec, s[4:5]
	v_lshlrev_b32_e32 v134, 11, v135
	v_add3_u32 v134, v136, v134, s95
	s_andn2_saveexec_b64 s[4:5], s[4:5]
	v_lshlrev_b32_e32 v134, 8, v135
	v_add3_u32 v134, v134, v136, s0
	s_or_b64 exec, exec, s[4:5]
	v_bfe_u32 v149, v140, 1, 5
	v_lshlrev_b32_e32 v135, 3, v140
	s_lshl_b32 s4, s20, 4
	v_and_b32_e32 v136, 8, v135
	v_add_u32_e32 v137, v134, v149
	v_mov_b64_e32 v[134:135], s[36:37]
	s_ashr_i32 s5, s4, 31
	v_mad_i64_i32 v[134:135], s[24:25], v137, s84, v[134:135]
	v_lshl_add_u64 v[134:135], s[4:5], 1, v[134:135]
	v_lshlrev_b32_e32 v144, 1, v136
	v_mov_b32_e32 v145, v1
	v_lshl_add_u64 v[134:135], v[134:135], 0, v[144:145]
	global_load_dwordx4 v[134:137], v[134:135], off offset:320
	v_add_u32_e32 v142, 0x200, v140
	v_ashrrev_i32_e32 v142, 6, v142
	v_subrev_u32_e32 v143, s19, v142
	v_add_u32_e32 v157, s7, v143
	v_subrev_u32_e32 v143, 35, v157
	v_mul_hi_i32 v143, v143, s94
	v_lshrrev_b32_e32 v145, 31, v143
	v_ashrrev_i32_e32 v143, 4, v143
	v_add_u32_e32 v143, v143, v145
	v_mul_lo_u32 v145, v143, s85
	v_sub_u32_e32 v145, v142, v145
	v_subrev_u32_e32 v145, s19, v145
	v_add_u32_e32 v145, s7, v145
	v_subrev_u32_e32 v145, 35, v145
	v_cmp_lt_i32_e32 vcc, 7, v145
	v_lshlrev_b32_e32 v146, 5, v145
	s_and_saveexec_b64 s[24:25], vcc
	s_xor_b64 s[24:25], exec, s[24:25]
	v_lshlrev_b32_e32 v143, 11, v143
	v_add3_u32 v145, v146, v143, s95
	s_andn2_saveexec_b64 s[24:25], s[24:25]
	v_lshlrev_b32_e32 v143, 8, v143
	v_add3_u32 v145, v143, v146, s0
	s_or_b64 exec, exec, s[24:25]
	v_add_u32_e32 v143, v145, v149
	v_mov_b64_e32 v[146:147], s[36:37]
	v_mad_i64_i32 v[146:147], s[24:25], v143, s84, v[146:147]
	v_lshl_add_u64 v[146:147], s[4:5], 1, v[146:147]
	v_mov_b32_e32 v145, v1
	v_lshl_add_u64 v[146:147], v[146:147], 0, v[144:145]
	global_load_dwordx4 v[158:161], v[146:147], off offset:320
	v_lshlrev_b32_e32 v140, 4, v140
	v_and_b32_e32 v140, 0x3f0, v140
	s_movk_i32 s14, 0x410
	v_add_u32_e32 v140, 0, v140
	v_mul_lo_u32 v141, v141, s14
	v_add_u32_e32 v147, v140, v141
	s_waitcnt vmcnt(0) lgkmcnt(0)
	ds_write_b128 v147, v[134:137]
	v_mul_lo_u32 v134, v142, s14
	v_subrev_u32_e32 v135, 19, v156
	v_add_u32_e32 v148, v140, v134
	v_mul_hi_i32 v134, v135, s94
	v_lshrrev_b32_e32 v136, 31, v134
	v_ashrrev_i32_e32 v134, 4, v134
	v_add_u32_e32 v134, v134, v136
	v_mul_lo_u32 v136, v134, s85
	v_sub_u32_e32 v135, v135, v136
	v_cmp_lt_i32_e32 vcc, 7, v135
	v_lshlrev_b32_e32 v136, 5, v135
	ds_write_b128 v148, v[158:161]
	s_waitcnt lgkmcnt(0)
	s_barrier
; #define LAS __attribute__((address_space(3)))
; #define MFMA16(a, b, c) __builtin_amdgcn_mfma_f32_16x16x32_bf16((a), (b), (c), 0, 0, 0)
; #define S5_LOAD(rb_) do { _Pragma("unroll") for (int j_ = 0; j_ < 3; ++j_) { const int p_ = tid + j_ * 512, rr_ = p_ / 96, kc_ = p_ % 96, r_ = (rb_) * 16 + rr_; \
;         st[j_] = kc_ < 64 ? ld8(P + (size_t)(tokbase_of(r_) + (kc_ >> 1)) * INP + OFF_S5 + g * 16 + (kc_ & 1) * 8) : ld8(S5H + ((size_t)r_ * 16 + g) * 256 + (kc_ - 64) * 8); } } while (0)
; #define S5_STORE(buf_) do { _Pragma("unroll") for (int j_ = 0; j_ < 3; ++j_) { const int p_ = tid + j_ * 512, rr_ = p_ / 96, kc_ = p_ % 96; *(LAS u32x4*)(lds + (buf_) * BUF + rr_ * RST + kc_ * 16) = st[j_]; } } while (0)
; #define S5_LOAD(rb_) do { _Pragma("unroll") for (int j_ = 0; j_ < 2; ++j_) { const int p_ = tid + j_ * 512, rr_ = p_ >> 6, kc_ = p_ & 63, r_ = (rb_) * 16 + rr_; \
;         st[j_] = ld8(P + (size_t)(tokbase_of(r_) + (kc_ >> 1)) * INP + OFF_S5 + g * 16 + (kc_ & 1) * 8); } } while (0)
; #define S5_STORE(buf_) do { _Pragma("unroll") for (int j_ = 0; j_ < 2; ++j_) { const int p_ = tid + j_ * 512, rr_ = p_ >> 6, kc_ = p_ & 63; *(LAS u32x4*)(lds + (buf_) * BUF + rr_ * RST + kc_ * 16) = st[j_]; } } while (0)
; __device__ __forceinline__ void s5_pass1_block(LAS unsigned char* lds, int bt, int l, const bf16_t* P, const bf16_t* WEND, float* S5S) {
;     ...
;     __syncthreads();
;     S5_LOAD(rg * 3);
;     for (int i = 0; i < 3; ++i) {
;         const int rb = rg * 3 + i;
;         S5_STORE(i & 1);
;         __syncthreads();
;         if (i < 2) S5_LOAD(rb + 1);
;         const LAS unsigned char* ab = lds + (i & 1) * BUF + fr * RST + fq * 16;
;         f32x4 acc0 = (f32x4){0.f, 0.f, 0.f, 0.f}, acc1 = acc0;
; #pragma unroll
;         for (int ks = 0; ks < 16; ++ks) { const bf16x8 af = *(const LAS bf16x8*)(ab + ks * 64); acc0 = MFMA16(af, bw[0][ks], acc0); acc1 = MFMA16(af, bw[1][ks], acc1); }
; #pragma unroll
;         for (int q = 0; q < 4; ++q) { float* o = S5S + ((size_t)(rb * 16 + fq * 4 + q) * 16 + g) * 256 + wave * 32 + fr; o[0] = acc0[q]; o[16] = acc1[q]; }
;     }
	s_and_saveexec_b64 s[24:25], vcc
	s_xor_b64 s[24:25], exec, s[24:25]
	v_lshlrev_b32_e32 v134, 11, v134
	v_add3_u32 v135, v136, v134, s95
	s_andn2_saveexec_b64 s[24:25], s[24:25]
	v_lshlrev_b32_e32 v134, 8, v134
	v_add3_u32 v135, v134, v136, s0
	s_or_b64 exec, exec, s[24:25]
	v_add_u32_e32 v136, v135, v149
	v_mov_b64_e32 v[134:135], s[36:37]
	v_mad_i64_i32 v[134:135], s[24:25], v136, s84, v[134:135]
	v_lshl_add_u64 v[134:135], s[4:5], 1, v[134:135]
	v_mov_b32_e32 v145, v1
	v_lshl_add_u64 v[134:135], v[134:135], 0, v[144:145]
	global_load_dwordx4 v[134:137], v[134:135], off offset:320
	v_subrev_u32_e32 v140, 19, v157
	v_mul_hi_i32 v141, v140, s94
	v_lshrrev_b32_e32 v142, 31, v141
	v_ashrrev_i32_e32 v141, 4, v141
	v_add_u32_e32 v141, v141, v142
	v_mul_lo_u32 v142, v141, s85
	v_sub_u32_e32 v140, v140, v142
	v_cmp_lt_i32_e32 vcc, 7, v140
	v_lshlrev_b32_e32 v142, 5, v140
	s_and_saveexec_b64 s[24:25], vcc
	s_xor_b64 s[24:25], exec, s[24:25]
	v_lshlrev_b32_e32 v140, 11, v141
	v_add3_u32 v140, v142, v140, s95
	s_andn2_saveexec_b64 s[24:25], s[24:25]
	v_lshlrev_b32_e32 v140, 8, v141
	v_add3_u32 v140, v140, v142, s0
	s_or_b64 exec, exec, s[24:25]
	v_mul_u32_u24_e32 v141, 0x410, v138
	v_add_u32_e32 v146, 0, v141
	v_add_u32_e32 v0, v146, v0
	ds_read_b128 v[158:161], v0
	ds_read_b128 v[166:169], v0 offset:64
	s_ashr_i32 s21, s20, 31
	s_lshl_b64 s[20:21], s[20:21], 10
	s_add_u32 s14, s1, s20
	s_addc_u32 s15, s6, s21
	s_lshl_b64 s[20:21], s[22:23], 2
	s_add_u32 s20, s14, s20
	v_lshlrev_b32_e32 v170, 2, v139
	s_waitcnt lgkmcnt(0)
	v_mfma_f32_16x16x32_bf16 v[162:165], v[158:161], v[118:121], 0
	s_addc_u32 s21, s15, s21
	v_lshlrev_b32_e32 v138, 2, v138
	v_mov_b32_e32 v139, v1
	v_mfma_f32_16x16x32_bf16 v[158:161], v[158:161], v[130:133], 0
	v_lshl_add_u64 v[142:143], s[20:21], 0, v[138:139]
	v_add_u32_e32 v140, v140, v149
	v_mov_b64_e32 v[138:139], s[36:37]
	v_mfma_f32_16x16x32_bf16 v[162:165], v[166:169], v[106:109], v[162:165]
	v_mad_i64_i32 v[138:139], s[20:21], v140, s84, v[138:139]
	v_lshl_add_u64 v[138:139], s[4:5], 1, v[138:139]
	v_mfma_f32_16x16x32_bf16 v[158:161], v[166:169], v[126:129], v[158:161]
	ds_read_b128 v[166:169], v0 offset:128
	v_mov_b32_e32 v145, v1
	v_lshl_add_u64 v[138:139], v[138:139], 0, v[144:145]
	s_waitcnt lgkmcnt(0)
	v_mfma_f32_16x16x32_bf16 v[162:165], v[166:169], v[102:105], v[162:165]
	global_load_dwordx4 v[138:141], v[138:139], off offset:320
	v_subrev_u32_e32 v145, s19, v170
	v_add_u32_e32 v146, s7, v145
	v_mfma_f32_16x16x32_bf16 v[158:161], v[166:169], v[122:125], v[158:161]
	ds_read_b128 v[166:169], v0 offset:192
	s_waitcnt lgkmcnt(0)
	v_mfma_f32_16x16x32_bf16 v[162:165], v[166:169], v[90:93], v[162:165]
	v_mfma_f32_16x16x32_bf16 v[158:161], v[166:169], v[114:117], v[158:161]
	ds_read_b128 v[166:169], v0 offset:256
	s_waitcnt lgkmcnt(0)
	v_mfma_f32_16x16x32_bf16 v[162:165], v[166:169], v[86:89], v[162:165]
	v_mfma_f32_16x16x32_bf16 v[158:161], v[166:169], v[110:113], v[158:161]
	ds_read_b128 v[166:169], v0 offset:320
	s_waitcnt lgkmcnt(0)
	v_mfma_f32_16x16x32_bf16 v[162:165], v[166:169], v[74:77], v[162:165]
	v_mfma_f32_16x16x32_bf16 v[158:161], v[166:169], v[98:101], v[158:161]
	ds_read_b128 v[166:169], v0 offset:384
	s_waitcnt lgkmcnt(0)
	v_mfma_f32_16x16x32_bf16 v[162:165], v[166:169], v[70:73], v[162:165]
	v_mfma_f32_16x16x32_bf16 v[158:161], v[166:169], v[94:97], v[158:161]
	ds_read_b128 v[166:169], v0 offset:448
	s_waitcnt lgkmcnt(0)
	v_mfma_f32_16x16x32_bf16 v[162:165], v[166:169], v[58:61], v[162:165]
	v_mfma_f32_16x16x32_bf16 v[158:161], v[166:169], v[82:85], v[158:161]
	ds_read_b128 v[166:169], v0 offset:512
	s_waitcnt lgkmcnt(0)
	v_mfma_f32_16x16x32_bf16 v[162:165], v[166:169], v[54:57], v[162:165]
	v_mfma_f32_16x16x32_bf16 v[158:161], v[166:169], v[78:81], v[158:161]
	ds_read_b128 v[166:169], v0 offset:576
	s_waitcnt lgkmcnt(0)
	v_mfma_f32_16x16x32_bf16 v[162:165], v[166:169], v[42:45], v[162:165]
	v_mfma_f32_16x16x32_bf16 v[158:161], v[166:169], v[66:69], v[158:161]
	ds_read_b128 v[166:169], v0 offset:640
	s_waitcnt lgkmcnt(0)
	v_mfma_f32_16x16x32_bf16 v[162:165], v[166:169], v[38:41], v[162:165]
	v_mfma_f32_16x16x32_bf16 v[158:161], v[166:169], v[62:65], v[158:161]
	ds_read_b128 v[166:169], v0 offset:704
	s_waitcnt lgkmcnt(0)
	v_mfma_f32_16x16x32_bf16 v[162:165], v[166:169], v[26:29], v[162:165]
	v_mfma_f32_16x16x32_bf16 v[158:161], v[166:169], v[50:53], v[158:161]
	ds_read_b128 v[166:169], v0 offset:768
	s_waitcnt lgkmcnt(0)
	v_mfma_f32_16x16x32_bf16 v[162:165], v[166:169], v[22:25], v[162:165]
	v_mfma_f32_16x16x32_bf16 v[158:161], v[166:169], v[46:49], v[158:161]
	ds_read_b128 v[166:169], v0 offset:832
	s_waitcnt lgkmcnt(0)
	v_mfma_f32_16x16x32_bf16 v[162:165], v[166:169], v[14:17], v[162:165]
	v_mfma_f32_16x16x32_bf16 v[158:161], v[166:169], v[34:37], v[158:161]
	ds_read_b128 v[166:169], v0 offset:896
	s_waitcnt lgkmcnt(0)
	v_mfma_f32_16x16x32_bf16 v[162:165], v[166:169], v[6:9], v[162:165]
	v_mfma_f32_16x16x32_bf16 v[158:161], v[166:169], v[30:33], v[158:161]
	ds_read_b128 v[166:169], v0 offset:960
	s_waitcnt lgkmcnt(0)
	v_mfma_f32_16x16x32_bf16 v[162:165], v[166:169], v[2:5], v[162:165]
	v_mfma_f32_16x16x32_bf16 v[158:161], v[166:169], v[18:21], v[158:161]
	v_subrev_u32_e32 v166, 35, v146
	v_ashrrev_i32_e32 v167, 31, v166
	v_lshlrev_b64 v[166:167], 14, v[166:167]
	v_lshl_add_u64 v[166:167], v[142:143], 0, v[166:167]
	s_nop 2
	global_store_dword v[166:167], v162, off
	global_store_dword v[166:167], v158, off offset:64
	v_subrev_u32_e32 v166, 34, v146
	v_ashrrev_i32_e32 v167, 31, v166
	v_lshlrev_b64 v[166:167], 14, v[166:167]
	v_lshl_add_u64 v[166:167], v[142:143], 0, v[166:167]
	v_subrev_u32_e32 v158, 33, v146
	global_store_dword v[166:167], v163, off
	global_store_dword v[166:167], v159, off offset:64
	v_ashrrev_i32_e32 v159, 31, v158
	v_lshlrev_b64 v[158:159], 14, v[158:159]
	v_lshl_add_u64 v[158:159], v[142:143], 0, v[158:159]
	global_store_dword v[158:159], v164, off
	global_store_dword v[158:159], v160, off offset:64
	v_subrev_u32_e32 v158, 32, v146
	v_ashrrev_i32_e32 v159, 31, v158
	v_lshlrev_b64 v[158:159], 14, v[158:159]
	v_lshl_add_u64 v[158:159], v[142:143], 0, v[158:159]
	global_store_dword v[158:159], v165, off
	global_store_dword v[158:159], v161, off offset:64
	s_waitcnt vmcnt(0)
	ds_write_b128 v147, v[134:137] offset:16640
	ds_write_b128 v148, v[138:141] offset:16640
	v_add_u32_e32 v135, -3, v156
	v_mul_hi_i32 v134, v135, s94
	v_lshrrev_b32_e32 v136, 31, v134
	v_ashrrev_i32_e32 v134, 4, v134
	v_add_u32_e32 v134, v134, v136
	v_mul_lo_u32 v136, v134, s85
	v_sub_u32_e32 v135, v135, v136
	v_cmp_lt_i32_e32 vcc, 7, v135
	v_lshlrev_b32_e32 v136, 5, v135
	s_waitcnt lgkmcnt(0)
	s_barrier
	s_and_saveexec_b64 s[20:21], vcc
	s_xor_b64 s[20:21], exec, s[20:21]
	v_lshlrev_b32_e32 v134, 11, v134
	v_add3_u32 v135, v136, v134, s95
	s_andn2_saveexec_b64 s[20:21], s[20:21]
	v_lshlrev_b32_e32 v134, 8, v134
	v_add3_u32 v135, v134, v136, s0
	s_or_b64 exec, exec, s[20:21]
	v_add_u32_e32 v136, v135, v149
	v_mov_b64_e32 v[134:135], s[36:37]
	v_mad_i64_i32 v[134:135], s[20:21], v136, s84, v[134:135]
	v_lshl_add_u64 v[134:135], s[4:5], 1, v[134:135]
	v_mov_b32_e32 v145, v1
	v_lshl_add_u64 v[134:135], v[134:135], 0, v[144:145]
	global_load_dwordx4 v[134:137], v[134:135], off offset:320
	v_add_u32_e32 v139, -3, v157
	v_mul_hi_i32 v138, v139, s94
	v_lshrrev_b32_e32 v140, 31, v138
	v_ashrrev_i32_e32 v138, 4, v138
	v_add_u32_e32 v138, v138, v140
	v_mul_lo_u32 v140, v138, s85
	v_sub_u32_e32 v139, v139, v140
	v_cmp_lt_i32_e32 vcc, 7, v139
	v_lshlrev_b32_e32 v140, 5, v139
	s_and_saveexec_b64 s[20:21], vcc
	s_xor_b64 s[20:21], exec, s[20:21]
	v_lshlrev_b32_e32 v138, 11, v138
	v_add3_u32 v139, v140, v138, s95
	s_andn2_saveexec_b64 s[20:21], s[20:21]
	s_cbranch_execz .LBB0_813
	v_lshlrev_b32_e32 v138, 8, v138
	v_add3_u32 v139, v138, v140, s0
	s_branch .LBB0_813

; #define LAS __attribute__((address_space(3)))
; __device__ __forceinline__ void pool_task(int b, int c, int gi, int l, const float* pool_b, const float* pool_s, LAS float* pl, const bf16_t* P, const bf16_t* WPOOL, bf16_t* Z3, int lane) {
;     ...
;     const int seqlen = c < 8 ? 256 : 2048, t0 = c < 8 ? c * 32 : (c - 8) * 32, rbase = c < 8 ? ML + b * 256 : b * 2048;
;     {
;         const int ch = gi * 64 + lane, half = 1 << gi;
;         const bf16_t* xp = P + (size_t)rbase * INP + OFF_POOL + ch;
;     ...
;         LAS bf16_t* xs16 = (LAS bf16_t*)(pl + 32 * 68);
;         { bf16_t xr[48];
; #pragma unroll
;         for (int s = 0; s < 48; ++s) { const int tt = t0 - 8 + s; xr[s] = (tt >= 0 && tt < seqlen) ? xp[(size_t)tt * INP] : (bf16_t)0; }
; __global__ void __launch_bounds__(512, 2) fwd_kernel(KArgs a) {
;     ...
;             { IDS; const int ncc = wctx ? NCH : 64; const int SP = NGW - NGW / 8, rk = gw - (gw >> 3) - 1, sh = (nKV > SP ? nKV - SP : 0) % SP;
;               const bool stdg = NGW == 2048; if (!stdg || (gw & 7)) for (int t = stdg ? (rk - sh + SP) % SP : gw; t < nPL; t += stdg ? SP : NGW) { const int gi = t & 3, cc = (t >> 2) % ncc, b = (t >> 2) / ncc;
;                 pool_task(b, wctx ? cc : cc + 8, gi, l, a.in[31], a.in[32], wscr, P, WPOOL, Z3, lane); } }
.LBB0_843:
	s_ashr_i32 s1, s20, 2
	s_abs_i32 s6, s1
	v_readlane_b32 s7, v250, 2
	s_mul_hi_u32 s7, s6, s7
	v_readlane_b32 s18, v250, 1
	s_mul_i32 s14, s7, s18
	s_sub_i32 s6, s6, s14
	s_ashr_i32 s5, s20, 31
	s_add_i32 s14, s7, 1
	s_sub_i32 s15, s6, s18
	s_cmp_ge_u32 s6, s18
	s_cselect_b32 s7, s14, s7
	s_cselect_b32 s6, s15, s6
	s_add_i32 s14, s7, 1
	s_cmp_ge_u32 s6, s18
	s_cselect_b32 s6, s14, s7
	s_xor_b32 s6, s6, s5
	s_sub_i32 s5, s6, s5
	s_mul_i32 s6, s5, s18
	s_sub_i32 s1, s1, s6
	v_readlane_b32 s6, v254, 55
	s_add_i32 s14, s1, 8
	v_readlane_b32 s7, v254, 56
	s_and_b64 s[6:7], s[6:7], exec
	s_cselect_b32 s1, s1, s14
	s_lshl_b32 s7, s1, 5
	s_lshl_b32 s6, s5, 8
	s_add_i32 s14, s7, 0xffffff00
	s_add_i32 s15, s6, 0x4000
	s_lshl_b32 s5, s5, 11
	s_cmp_lt_i32 s1, 8
	s_movk_i32 s1, 0x800
	s_cselect_b32 s6, 0x100, s1
	s_cselect_b32 s1, s7, s14
	s_cselect_b32 s5, s15, s5
	s_add_i32 s7, s1, -8
	v_mad_i64_i32 v[2:3], s[18:19], s5, v202, v[38:39]
	v_mov_b32_e32 v4, 0
	s_cmp_ge_u32 s7, s6
	v_mov_b32_e32 v5, 0
	s_cbranch_scc1 .LBB0_845
	v_mad_u64_u32 v[6:7], s[18:19], s7, v202, v[2:3]
	global_load_ushort v5, v[6:7], off offset:1856
.LBB0_845:
	s_add_i32 s7, s1, -7
	s_cmp_ge_u32 s7, s6
	s_cbranch_scc1 .LBB0_847
	v_mad_u64_u32 v[6:7], s[18:19], s7, v202, v[2:3]
	global_load_ushort v4, v[6:7], off offset:1856
.LBB0_847:
	s_add_i32 s7, s1, -6
	v_mov_b32_e32 v6, 0
	s_cmp_ge_u32 s7, s6
	v_mov_b32_e32 v7, 0
	s_cbranch_scc1 .LBB0_849
	v_mad_u64_u32 v[8:9], s[18:19], s7, v202, v[2:3]
	global_load_ushort v7, v[8:9], off offset:1856
.LBB0_849:
	s_add_i32 s7, s1, -5
	s_cmp_ge_u32 s7, s6
	s_cbranch_scc1 .LBB0_851
	v_mad_u64_u32 v[8:9], s[18:19], s7, v202, v[2:3]
	global_load_ushort v6, v[8:9], off offset:1856
.LBB0_851:
	s_add_i32 s7, s1, -4
	v_mov_b32_e32 v8, 0
	s_cmp_ge_u32 s7, s6
	v_mov_b32_e32 v9, 0
	s_cbranch_scc1 .LBB0_853
	v_mad_u64_u32 v[14:15], s[18:19], s7, v202, v[2:3]
	global_load_ushort v9, v[14:15], off offset:1856
.LBB0_853:
	s_add_i32 s7, s1, -3
	s_cmp_ge_u32 s7, s6
	s_cbranch_scc1 .LBB0_855
	v_mad_u64_u32 v[14:15], s[18:19], s7, v202, v[2:3]
	global_load_ushort v8, v[14:15], off offset:1856
.LBB0_855:
	s_add_i32 s7, s1, -2
	v_mov_b32_e32 v14, 0
	s_cmp_ge_u32 s7, s6
	v_mov_b32_e32 v15, 0
	s_cbranch_scc1 .LBB0_859
	v_mad_u64_u32 v[16:17], s[18:19], s7, v202, v[2:3]
	global_load_ushort v15, v[16:17], off offset:1856
	s_add_i32 s7, s1, -1
	s_cmp_ge_u32 s7, s6
	s_cbranch_scc0 .LBB0_860

; __device__ __forceinline__ void pool_task(int b, int c, int gi, int l, const float* pool_b, const float* pool_s, LAS float* pl, const bf16_t* P, const bf16_t* WPOOL, bf16_t* Z3, int lane) {
;     ...
;         { bf16_t xr[48];
; #pragma unroll
;         for (int s = 0; s < 48; ++s) { const int tt = t0 - 8 + s; xr[s] = (tt >= 0 && tt < seqlen) ? xp[(size_t)tt * INP] : (bf16_t)0; }
.LBB0_858:
	v_mad_u64_u32 v[18:19], s[18:19], s1, v202, v[2:3]
	global_load_ushort v17, v[18:19], off offset:1856
	s_or_b32 s7, s1, 1
	s_cmp_ge_u32 s7, s6
	s_cbranch_scc0 .LBB0_862
	s_branch .LBB0_863

; __device__ __forceinline__ void pool_task(int b, int c, int gi, int l, const float* pool_b, const float* pool_s, LAS float* pl, const bf16_t* P, const bf16_t* WPOOL, bf16_t* Z3, int lane) {
;     ...
;         { bf16_t xr[48];
; #pragma unroll
;         for (int s = 0; s < 48; ++s) { const int tt = t0 - 8 + s; xr[s] = (tt >= 0 && tt < seqlen) ? xp[(size_t)tt * INP] : (bf16_t)0; }
.LBB0_860:
	v_mad_u64_u32 v[16:17], s[18:19], s7, v202, v[2:3]
	global_load_ushort v14, v[16:17], off offset:1856
	v_mov_b32_e32 v16, 0
	s_cmp_ge_u32 s1, s6
	v_mov_b32_e32 v17, 0
	s_cbranch_scc0 .LBB0_858

; __device__ __forceinline__ void pool_task(int b, int c, int gi, int l, const float* pool_b, const float* pool_s, LAS float* pl, const bf16_t* P, const bf16_t* WPOOL, bf16_t* Z3, int lane) {
;     ...
;         { bf16_t xr[48];
; #pragma unroll
;         for (int s = 0; s < 48; ++s) { const int tt = t0 - 8 + s; xr[s] = (tt >= 0 && tt < seqlen) ? xp[(size_t)tt * INP] : (bf16_t)0; }
.LBB0_862:
	v_mad_u64_u32 v[18:19], s[18:19], s7, v202, v[2:3]
	global_load_ushort v16, v[18:19], off offset:1856
.LBB0_863:
	s_or_b32 s7, s1, 2
	v_mov_b32_e32 v18, 0
	s_cmp_ge_u32 s7, s6
	v_mov_b32_e32 v19, 0
	s_cbranch_scc1 .LBB0_865
	v_mad_u64_u32 v[20:21], s[18:19], s7, v202, v[2:3]
	global_load_ushort v19, v[20:21], off offset:1856
.LBB0_865:
	s_or_b32 s7, s1, 3
	s_cmp_ge_u32 s7, s6
	s_cbranch_scc1 .LBB0_867
	v_mad_u64_u32 v[20:21], s[18:19], s7, v202, v[2:3]
	global_load_ushort v18, v[20:21], off offset:1856
.LBB0_867:
	s_or_b32 s7, s1, 4
	v_mov_b32_e32 v20, 0
	s_cmp_ge_u32 s7, s6
	v_mov_b32_e32 v21, 0
	s_cbranch_scc1 .LBB0_869
	v_mad_u64_u32 v[46:47], s[18:19], s7, v202, v[2:3]
	global_load_ushort v21, v[46:47], off offset:1856
.LBB0_869:
	s_or_b32 s7, s1, 5
	s_cmp_ge_u32 s7, s6
	s_cbranch_scc1 .LBB0_871
	v_mad_u64_u32 v[46:47], s[18:19], s7, v202, v[2:3]
	global_load_ushort v20, v[46:47], off offset:1856
.LBB0_871:
	s_or_b32 s7, s1, 6
	v_mov_b32_e32 v43, 0
	s_cmp_ge_u32 s7, s6
	v_mov_b32_e32 v45, 0
	s_cbranch_scc1 .LBB0_873
	v_mad_u64_u32 v[46:47], s[18:19], s7, v202, v[2:3]
	global_load_ushort v45, v[46:47], off offset:1856
.LBB0_873:
	s_or_b32 s7, s1, 7
	s_cmp_ge_u32 s7, s6
	s_cbranch_scc1 .LBB0_875
	v_mad_u64_u32 v[46:47], s[18:19], s7, v202, v[2:3]
	global_load_ushort v43, v[46:47], off offset:1856
.LBB0_875:
	s_or_b32 s7, s1, 8
	v_mov_b32_e32 v46, 0
	s_cmp_ge_u32 s7, s6
	v_mov_b32_e32 v47, 0
	s_cbranch_scc1 .LBB0_877
	v_mad_u64_u32 v[48:49], s[18:19], s7, v202, v[2:3]
	global_load_ushort v47, v[48:49], off offset:1856
.LBB0_877:
	s_or_b32 s7, s1, 9
	s_cmp_ge_u32 s7, s6
	s_cbranch_scc1 .LBB0_879
	v_mad_u64_u32 v[48:49], s[18:19], s7, v202, v[2:3]
	global_load_ushort v46, v[48:49], off offset:1856
.LBB0_879:
	s_or_b32 s7, s1, 10
	v_mov_b32_e32 v48, 0
	s_cmp_ge_u32 s7, s6
	v_mov_b32_e32 v49, 0
	s_cbranch_scc1 .LBB0_881
	v_mad_u64_u32 v[50:51], s[18:19], s7, v202, v[2:3]
	global_load_ushort v49, v[50:51], off offset:1856
.LBB0_881:
	s_or_b32 s7, s1, 11
	s_cmp_ge_u32 s7, s6
	s_cbranch_scc1 .LBB0_883
	v_mad_u64_u32 v[50:51], s[18:19], s7, v202, v[2:3]
	global_load_ushort v48, v[50:51], off offset:1856
.LBB0_883:
	s_or_b32 s7, s1, 12
	v_mov_b32_e32 v50, 0
	s_cmp_ge_u32 s7, s6
	v_mov_b32_e32 v51, 0
	s_cbranch_scc1 .LBB0_885
	v_mad_u64_u32 v[52:53], s[18:19], s7, v202, v[2:3]
	global_load_ushort v51, v[52:53], off offset:1856
.LBB0_885:
	s_or_b32 s7, s1, 13
	s_cmp_ge_u32 s7, s6
	s_cbranch_scc1 .LBB0_887
	v_mad_u64_u32 v[52:53], s[18:19], s7, v202, v[2:3]
	global_load_ushort v50, v[52:53], off offset:1856
.LBB0_887:
	s_or_b32 s7, s1, 14
	v_mov_b32_e32 v52, 0
	s_cmp_ge_u32 s7, s6
	v_mov_b32_e32 v53, 0
	s_cbranch_scc1 .LBB0_889
	v_mad_u64_u32 v[54:55], s[18:19], s7, v202, v[2:3]
	global_load_ushort v53, v[54:55], off offset:1856
.LBB0_889:
	s_or_b32 s7, s1, 15
	s_cmp_ge_u32 s7, s6
	s_cbranch_scc1 .LBB0_891
	v_mad_u64_u32 v[54:55], s[18:19], s7, v202, v[2:3]
	global_load_ushort v52, v[54:55], off offset:1856
.LBB0_891:
	s_or_b32 s7, s1, 16
	v_mov_b32_e32 v54, 0
	s_cmp_ge_u32 s7, s6
	v_mov_b32_e32 v55, 0
	s_cbranch_scc1 .LBB0_893
	v_mad_u64_u32 v[56:57], s[18:19], s7, v202, v[2:3]
	global_load_ushort v55, v[56:57], off offset:1856
.LBB0_893:
	s_or_b32 s7, s1, 17
	s_cmp_ge_u32 s7, s6
	s_cbranch_scc1 .LBB0_895
	v_mad_u64_u32 v[56:57], s[18:19], s7, v202, v[2:3]
	global_load_ushort v54, v[56:57], off offset:1856
.LBB0_895:
	s_or_b32 s7, s1, 18
	v_mov_b32_e32 v56, 0
	s_cmp_ge_u32 s7, s6
	v_mov_b32_e32 v57, 0
	s_cbranch_scc1 .LBB0_897
	v_mad_u64_u32 v[58:59], s[18:19], s7, v202, v[2:3]
	global_load_ushort v57, v[58:59], off offset:1856
.LBB0_897:
	s_or_b32 s7, s1, 19
	s_cmp_ge_u32 s7, s6
	s_cbranch_scc1 .LBB0_899
	v_mad_u64_u32 v[58:59], s[18:19], s7, v202, v[2:3]
	global_load_ushort v56, v[58:59], off offset:1856
.LBB0_899:
	s_or_b32 s7, s1, 20
	v_mov_b32_e32 v58, 0
	s_cmp_ge_u32 s7, s6
	v_mov_b32_e32 v59, 0
	s_cbranch_scc1 .LBB0_901
	v_mad_u64_u32 v[60:61], s[18:19], s7, v202, v[2:3]
	global_load_ushort v59, v[60:61], off offset:1856
; __device__ __forceinline__ void pool_task(int b, int c, int gi, int l, const float* pool_b, const float* pool_s, LAS float* pl, const bf16_t* P, const bf16_t* WPOOL, bf16_t* Z3, int lane) {
;     ...
;         { bf16_t xr[48];
; #pragma unroll
;         for (int s = 0; s < 48; ++s) { const int tt = t0 - 8 + s; xr[s] = (tt >= 0 && tt < seqlen) ? xp[(size_t)tt * INP] : (bf16_t)0; }
; #pragma unroll
;         for (int s = 0; s < 48; ++s) xs16[s * 64 + lane] = xr[s]; }
.LBB0_901:
	s_or_b32 s7, s1, 21
	s_cmp_ge_u32 s7, s6
	s_cbranch_scc1 .LBB0_903
	v_mad_u64_u32 v[60:61], s[18:19], s7, v202, v[2:3]
	global_load_ushort v58, v[60:61], off offset:1856
.LBB0_903:
	s_or_b32 s7, s1, 22
	v_mov_b32_e32 v60, 0
	s_cmp_ge_u32 s7, s6
	v_mov_b32_e32 v61, 0
	s_cbranch_scc1 .LBB0_905
	v_mad_u64_u32 v[62:63], s[18:19], s7, v202, v[2:3]
	global_load_ushort v61, v[62:63], off offset:1856
.LBB0_905:
	s_or_b32 s7, s1, 23
	s_cmp_ge_u32 s7, s6
	s_cbranch_scc1 .LBB0_907
	v_mad_u64_u32 v[62:63], s[18:19], s7, v202, v[2:3]
	global_load_ushort v60, v[62:63], off offset:1856
.LBB0_907:
	s_or_b32 s7, s1, 24
	v_mov_b32_e32 v62, 0
	s_cmp_ge_u32 s7, s6
	v_mov_b32_e32 v63, 0
	s_cbranch_scc1 .LBB0_909
	v_mad_u64_u32 v[64:65], s[18:19], s7, v202, v[2:3]
	global_load_ushort v63, v[64:65], off offset:1856
.LBB0_909:
	s_or_b32 s7, s1, 25
	s_cmp_ge_u32 s7, s6
	s_cbranch_scc1 .LBB0_911
	v_mad_u64_u32 v[64:65], s[18:19], s7, v202, v[2:3]
	global_load_ushort v62, v[64:65], off offset:1856
.LBB0_911:
	s_or_b32 s7, s1, 26
	v_mov_b32_e32 v64, 0
	s_cmp_ge_u32 s7, s6
	v_mov_b32_e32 v65, 0
	s_cbranch_scc1 .LBB0_913
	v_mad_u64_u32 v[74:75], s[18:19], s7, v202, v[2:3]
	global_load_ushort v65, v[74:75], off offset:1856
.LBB0_913:
	s_or_b32 s7, s1, 27
	s_cmp_ge_u32 s7, s6
	s_cbranch_scc1 .LBB0_915
	v_mad_u64_u32 v[74:75], s[18:19], s7, v202, v[2:3]
	global_load_ushort v64, v[74:75], off offset:1856
.LBB0_915:
	s_or_b32 s7, s1, 28
	v_mov_b32_e32 v74, 0
	s_cmp_ge_u32 s7, s6
	v_mov_b32_e32 v75, 0
	s_cbranch_scc1 .LBB0_917
	v_mad_u64_u32 v[76:77], s[18:19], s7, v202, v[2:3]
	global_load_ushort v75, v[76:77], off offset:1856
.LBB0_917:
	s_or_b32 s7, s1, 29
	s_cmp_ge_u32 s7, s6
	s_cbranch_scc1 .LBB0_919
	v_mad_u64_u32 v[76:77], s[18:19], s7, v202, v[2:3]
	global_load_ushort v74, v[76:77], off offset:1856
.LBB0_919:
	s_or_b32 s7, s1, 30
	v_mov_b32_e32 v76, 0
	s_cmp_ge_u32 s7, s6
	v_mov_b32_e32 v77, 0
	s_cbranch_scc1 .LBB0_921
	v_mad_u64_u32 v[78:79], s[18:19], s7, v202, v[2:3]
	global_load_ushort v77, v[78:79], off offset:1856
.LBB0_921:
	s_or_b32 s7, s1, 31
	s_cmp_ge_u32 s7, s6
	s_cbranch_scc1 .LBB0_923
	v_mad_u64_u32 v[78:79], s[18:19], s7, v202, v[2:3]
	global_load_ushort v76, v[78:79], off offset:1856
.LBB0_923:
	s_add_i32 s7, s1, 32
	v_mov_b32_e32 v78, 0
	s_cmp_ge_u32 s7, s6
	v_mov_b32_e32 v79, 0
	s_cbranch_scc1 .LBB0_925
	v_mad_u64_u32 v[80:81], s[18:19], s7, v202, v[2:3]
	global_load_ushort v79, v[80:81], off offset:1856
.LBB0_925:
	s_add_i32 s7, s1, 33
	s_cmp_ge_u32 s7, s6
	s_cbranch_scc1 .LBB0_927
	v_mad_u64_u32 v[80:81], s[18:19], s7, v202, v[2:3]
	global_load_ushort v78, v[80:81], off offset:1856
.LBB0_927:
	s_add_i32 s7, s1, 34
	v_mov_b32_e32 v80, 0
	s_cmp_ge_u32 s7, s6
	v_mov_b32_e32 v81, 0
	s_cbranch_scc1 .LBB0_929
	v_mad_u64_u32 v[82:83], s[18:19], s7, v202, v[2:3]
	global_load_ushort v81, v[82:83], off offset:1856
.LBB0_929:
	s_add_i32 s7, s1, 35
	s_cmp_ge_u32 s7, s6
	s_cbranch_scc1 .LBB0_931
	v_mad_u64_u32 v[82:83], s[18:19], s7, v202, v[2:3]
	global_load_ushort v80, v[82:83], off offset:1856
.LBB0_931:
	s_add_i32 s7, s1, 36
	v_mov_b32_e32 v82, 0
	s_cmp_ge_u32 s7, s6
	v_mov_b32_e32 v83, 0
	s_cbranch_scc1 .LBB0_933
	v_mad_u64_u32 v[84:85], s[18:19], s7, v202, v[2:3]
	global_load_ushort v83, v[84:85], off offset:1856
.LBB0_933:
	s_add_i32 s7, s1, 37
	s_cmp_ge_u32 s7, s6
	s_cbranch_scc1 .LBB0_935
	v_mad_u64_u32 v[84:85], s[18:19], s7, v202, v[2:3]
	global_load_ushort v82, v[84:85], off offset:1856
.LBB0_935:
	s_add_i32 s7, s1, 38
	v_mov_b32_e32 v84, 0
	s_cmp_ge_u32 s7, s6
	v_mov_b32_e32 v85, 0
	s_cbranch_scc1 .LBB0_937
	v_mad_u64_u32 v[86:87], s[18:19], s7, v202, v[2:3]
	global_load_ushort v85, v[86:87], off offset:1856
.LBB0_937:
	s_add_i32 s7, s1, 39
	s_cmp_ge_u32 s7, s6
	s_cbranch_scc1 .LBB0_939
	v_mad_u64_u32 v[2:3], s[18:19], s7, v202, v[2:3]
	global_load_ushort v84, v[2:3], off offset:1856

; #define MFMA16(a, b, c) __builtin_amdgcn_mfma_f32_16x16x32_bf16((a), (b), (c), 0, 0, 0)
; #define LXS(tt) bf1(xs16[((tt) - t0 + 8) * 64 + lane])
; __device__ __forceinline__ void pool_task(int b, int c, int gi, int l, const float* pool_b, const float* pool_s, LAS float* pl, const bf16_t* P, const bf16_t* WPOOL, bf16_t* Z3, int lane) {
;     ...
;         float sum = 0.f;
;         for (int tt = t0 - half; tt < t0 + half; ++tt) sum += LXS(tt);
;         for (int s = 0; s < 32; ++s) { const int tt = t0 + s; const int lo = max(tt - half, 0), hi = min(tt + half, seqlen);
;             const float xv = LXS(tt); pl[s * 68 + lane] = sum * __builtin_amdgcn_rcpf((float)(hi - lo)) - xv;
;             sum += LXS(tt + half) - LXS(tt - half); }
;     ...
;     }
;     asm volatile("s_waitcnt lgkmcnt(0)" ::: "memory");
;     bf16x8 bfr[2][2];
; #pragma unroll
;     for (int tb = 0; tb < 2; ++tb)
; #pragma unroll
;         for (int ks = 0; ks < 2; ++ks) bfr[tb][ks] = pack8(pl + (tb * 16 + fr) * 68 + ks * 32 + fq * 8);
;     u32x2 pgv[4][2];
; #pragma unroll
;     for (int cb = 0; cb < 4; ++cb)
; #pragma unroll
;         for (int tb = 0; tb < 2; ++tb) pgv[cb][tb] = ld4(P + (size_t)(rbase + t0 + tb * 16 + fr) * INP + OFF_GATE + 3 * 256 + gi * 64 + cb * 16 + fq * 4);
; #pragma unroll
;     for (int cb = 0; cb < 4; ++cb) {
;         const bf16_t* wp = WPOOL + ((size_t)(l * 4 + gi) * 64 + cb * 16 + fr) * 64 + fq * 8;
;         const bf16x8 w0 = asfrag(ld8(wp)), w1 = asfrag(ld8(wp + 32));
;         const int o4 = gi * 64 + cb * 16 + fq * 4;
;         const f32x4 pb = *(const f32x4*)(pool_b + l * 256 + o4), ps = *(const f32x4*)(pool_s + l * 256 + o4);
; #pragma unroll
;         for (int tb = 0; tb < 2; ++tb) { f32x4 acc = (f32x4){0.f, 0.f, 0.f, 0.f}; acc = MFMA16(w0, bfr[tb][0], acc); acc = MFMA16(w1, bfr[tb][1], acc);
;             const size_t row = (size_t)(rbase + t0 + tb * 16 + fr); const u32x2 g = pgv[cb][tb];
.LBB0_943:
	s_add_i32 s14, s7, s19
	s_add_i32 s22, s18, s19
	s_max_i32 s15, s14, 0
	s_min_i32 s23, s22, s6
	s_sub_i32 s15, s23, s15
	v_add_u32_e32 v14, s21, v5
	v_add_u32_e32 v16, s21, v4
	v_cvt_f32_i32_e32 v9, s15
	ds_read_u16 v15, v14
	ds_read_u16 v17, v16
	v_add_u32_e32 v7, s21, v3
	ds_read_u16 v8, v7
	s_add_i32 s15, s14, 1
	s_add_i32 s23, s22, 1
	v_rcp_iflag_f32_e32 v9, v9
	s_max_i32 s15, s15, 0
	s_min_i32 s23, s23, s6
	s_waitcnt lgkmcnt(2)
	v_lshlrev_b32_e32 v15, 16, v15
	s_waitcnt lgkmcnt(1)
	v_lshlrev_b32_e32 v17, 16, v17
	s_sub_i32 s15, s23, s15
	v_sub_f32_e32 v15, v15, v17
	v_cvt_f32_i32_e32 v17, s15
	s_waitcnt lgkmcnt(0)
	v_lshlrev_b32_e32 v8, 16, v8
	v_fma_f32 v8, v6, v9, -v8
	v_add_f32_e32 v6, v6, v15
	ds_read_u16 v15, v7 offset:128
	v_rcp_iflag_f32_e32 v17, v17
	v_add_u32_e32 v9, s21, v2
	s_add_i32 s15, s14, 2
	s_add_i32 s23, s22, 2
	s_waitcnt lgkmcnt(0)
	v_lshlrev_b32_e32 v15, 16, v15
	v_fma_f32 v15, v6, v17, -v15
	ds_write2_b32 v9, v8, v15 offset1:68
	ds_read_u16 v8, v14 offset:128
	ds_read_u16 v15, v16 offset:128
	ds_read_u16 v17, v16 offset:256
	s_max_i32 s15, s15, 0
	s_min_i32 s23, s23, s6
	s_waitcnt lgkmcnt(2)
	v_lshlrev_b32_e32 v8, 16, v8
	s_waitcnt lgkmcnt(1)
	v_lshlrev_b32_e32 v15, 16, v15
	s_sub_i32 s15, s23, s15
	v_sub_f32_e32 v8, v8, v15
	v_cvt_f32_i32_e32 v15, s15
	v_add_f32_e32 v6, v6, v8
	ds_read_u16 v8, v7 offset:256
	s_add_i32 s14, s14, 3
	v_rcp_iflag_f32_e32 v15, v15
	s_add_i32 s22, s22, 3
	s_waitcnt lgkmcnt(1)
	v_lshlrev_b32_e32 v17, 16, v17
	s_waitcnt lgkmcnt(0)
	v_lshlrev_b32_e32 v8, 16, v8
	v_fma_f32 v8, v6, v15, -v8
	ds_read_u16 v15, v14 offset:256
	s_max_i32 s14, s14, 0
	s_min_i32 s15, s22, s6
	s_sub_i32 s14, s15, s14
	ds_read_u16 v7, v7 offset:384
	s_waitcnt lgkmcnt(1)
	v_lshlrev_b32_e32 v15, 16, v15
	v_sub_f32_e32 v15, v15, v17
	v_add_f32_e32 v6, v6, v15
	v_cvt_f32_i32_e32 v15, s14
	s_waitcnt lgkmcnt(0)
	v_lshlrev_b32_e32 v7, 16, v7
	s_add_i32 s19, s19, 4
	v_add_u32_e32 v5, 0x200, v5
	v_rcp_iflag_f32_e32 v15, v15
	v_add_u32_e32 v4, 0x200, v4
	v_add_u32_e32 v3, 0x200, v3
	v_add_u32_e32 v2, 0x440, v2
	v_fma_f32 v7, v6, v15, -v7
	ds_write2_b32 v9, v8, v7 offset0:136 offset1:204
	ds_read_u16 v7, v14 offset:384
	ds_read_u16 v8, v16 offset:384
	s_cmp_lg_u32 s19, 32
	s_waitcnt lgkmcnt(1)
	v_lshlrev_b32_e32 v7, 16, v7
	s_waitcnt lgkmcnt(0)
	v_lshlrev_b32_e32 v8, 16, v8
	v_sub_f32_e32 v7, v7, v8
	v_add_f32_e32 v6, v6, v7
	s_cbranch_scc1 .LBB0_943
	s_waitcnt lgkmcnt(0)
	ds_read_b64 v[2:3], v73
	s_waitcnt lgkmcnt(0)
	v_cvt_pk_bf16_f32 v14, v2, v3
	ds_read_b64 v[2:3], v73 offset:8
	s_waitcnt lgkmcnt(0)
	v_cvt_pk_bf16_f32 v15, v2, v3
	ds_read_b64 v[2:3], v73 offset:16
	s_waitcnt lgkmcnt(0)
	v_cvt_pk_bf16_f32 v16, v2, v3
	ds_read_b64 v[2:3], v73 offset:24
	s_waitcnt lgkmcnt(0)
	v_cvt_pk_bf16_f32 v17, v2, v3
	ds_read_b64 v[2:3], v73 offset:128
	s_waitcnt lgkmcnt(0)
	v_cvt_pk_bf16_f32 v18, v2, v3
	ds_read_b64 v[2:3], v73 offset:136
	s_waitcnt lgkmcnt(0)
	v_cvt_pk_bf16_f32 v19, v2, v3
	ds_read_b64 v[2:3], v73 offset:144
	s_waitcnt lgkmcnt(0)
	v_cvt_pk_bf16_f32 v20, v2, v3
	ds_read_b64 v[2:3], v73 offset:152
	s_waitcnt lgkmcnt(0)
	v_cvt_pk_bf16_f32 v21, v2, v3
	ds_read_b64 v[2:3], v73 offset:4352
	s_waitcnt lgkmcnt(0)
	v_cvt_pk_bf16_f32 v2, v2, v3
	ds_read_b64 v[4:5], v73 offset:4360
	s_waitcnt lgkmcnt(0)
	v_cvt_pk_bf16_f32 v3, v4, v5
	ds_read_b64 v[4:5], v73 offset:4368
	s_waitcnt lgkmcnt(0)
	v_cvt_pk_bf16_f32 v4, v4, v5
	ds_read_b64 v[6:7], v73 offset:4376
	s_waitcnt lgkmcnt(0)
	v_cvt_pk_bf16_f32 v5, v6, v7
	ds_read_b64 v[6:7], v73 offset:4480
	s_waitcnt lgkmcnt(0)
	v_cvt_pk_bf16_f32 v6, v6, v7
	ds_read_b64 v[8:9], v73 offset:4488
	s_waitcnt lgkmcnt(0)
	v_cvt_pk_bf16_f32 v7, v8, v9
	ds_read_b64 v[8:9], v73 offset:4496
	s_add_i32 s1, s1, s5
	s_waitcnt lgkmcnt(0)
	v_cvt_pk_bf16_f32 v8, v8, v9
	ds_read_b64 v[46:47], v73 offset:4504
	v_or_b32_e32 v60, s1, v67
	s_waitcnt lgkmcnt(0)
	v_cvt_pk_bf16_f32 v9, v46, v47
	v_mad_i64_i32 v[46:47], s[6:7], v60, s84, v[40:41]
	global_load_dwordx2 v[64:65], v[46:47], off offset:3904
	v_or_b32_e32 v58, 16, v60
	v_mad_i64_i32 v[74:75], s[6:7], v58, s84, v[40:41]
	global_load_dwordx2 v[62:63], v[74:75], off offset:3904
	global_load_dwordx2 v[54:55], v[46:47], off offset:3936
	global_load_dwordx2 v[56:57], v[74:75], off offset:3936
	global_load_dwordx2 v[52:53], v[46:47], off offset:3968
	global_load_dwordx2 v[50:51], v[74:75], off offset:3968
	global_load_dwordx2 v[48:49], v[46:47], off offset:4000
	s_nop 0
	global_load_dwordx2 v[46:47], v[74:75], off offset:4000
	s_nop 0
	global_load_dwordx4 v[74:77], v[22:23], off
	global_load_dwordx4 v[78:81], v[22:23], off offset:64
	global_load_dwordx4 v[82:85], v[24:25], off
	global_load_dwordx4 v[86:89], v[26:27], off
	v_ashrrev_i32_e32 v61, 31, v60
	v_lshlrev_b64 v[60:61], 9, v[60:61]
	v_ashrrev_i32_e32 v59, 31, v58
	v_lshlrev_b64 v[58:59], 9, v[58:59]
	s_add_i32 s20, s20, s24
	v_readlane_b32 s1, v254, 18
	s_cmp_lt_i32 s20, s1
	s_waitcnt vmcnt(0) lgkmcnt(0)
; __device__ __forceinline__ unsigned cvt_pk_bf16(float lo, float hi) { unsigned r; asm volatile("v_cvt_pk_bf16_f32 %0, %1, %2" : "=v"(r) : "v"(lo), "v"(hi)); return r; }
; __device__ __forceinline__ float bflo(unsigned w) { return __uint_as_float(w << 16); }
; __device__ __forceinline__ float bfhi(unsigned w) { return __uint_as_float(w & 0xffff0000u); }
; __device__ __forceinline__ float siluf(float x) { return x * __builtin_amdgcn_rcpf(1.f + __expf(-x)); }
; #define MFMA16(a, b, c) __builtin_amdgcn_mfma_f32_16x16x32_bf16((a), (b), (c), 0, 0, 0)
; __device__ __forceinline__ void pool_task(int b, int c, int gi, int l, const float* pool_b, const float* pool_s, LAS float* pl, const bf16_t* P, const bf16_t* WPOOL, bf16_t* Z3, int lane) {
;     ...
;     for (int cb = 0; cb < 4; ++cb) {
;         const bf16_t* wp = WPOOL + ((size_t)(l * 4 + gi) * 64 + cb * 16 + fr) * 64 + fq * 8;
;         const bf16x8 w0 = asfrag(ld8(wp)), w1 = asfrag(ld8(wp + 32));
;         const int o4 = gi * 64 + cb * 16 + fq * 4;
;         const f32x4 pb = *(const f32x4*)(pool_b + l * 256 + o4), ps = *(const f32x4*)(pool_s + l * 256 + o4);
; #pragma unroll
;         for (int tb = 0; tb < 2; ++tb) { f32x4 acc = (f32x4){0.f, 0.f, 0.f, 0.f}; acc = MFMA16(w0, bfr[tb][0], acc); acc = MFMA16(w1, bfr[tb][1], acc);
;             const size_t row = (size_t)(rbase + t0 + tb * 16 + fr); const u32x2 g = pgv[cb][tb];
;             f32x4 v = (acc + pb) * ps; v[0] *= siluf(bflo(g.x)); v[1] *= siluf(bfhi(g.x)); v[2] *= siluf(bflo(g.y)); v[3] *= siluf(bfhi(g.y));
;             u32x2 w; w.x = cvt_pk_bf16(v[0], v[1]); w.y = cvt_pk_bf16(v[2], v[3]); *(u32x2*)(Z3 + row * 256 + o4) = w; }
	v_mfma_f32_16x16x32_bf16 v[90:93], v[74:77], v[14:17], 0
	v_lshlrev_b32_e32 v43, 16, v64
	v_mul_f32_e32 v45, 0xbfb8aa3b, v43
	v_exp_f32_e32 v45, v45
	v_mfma_f32_16x16x32_bf16 v[90:93], v[78:81], v[18:21], v[90:93]
	v_add_f32_e32 v45, 1.0, v45
	v_rcp_f32_e32 v45, v45
	v_mfma_f32_16x16x32_bf16 v[74:77], v[74:77], v[2:5], 0
	s_nop 4
	v_add_f32_e64 v90, v82, v90
	v_add_f32_e64 v91, v83, v91
	v_pk_add_f32 v[92:93], v[84:85], v[92:93]
	v_mul_f32_e32 v43, v45, v43
	v_and_b32_e32 v45, 0xffff0000, v64
	v_mul_f32_e32 v64, 0xbfb8aa3b, v45
	v_exp_f32_e32 v64, v64
	v_pk_mul_f32 v[90:91], v[86:87], v[90:91]
	v_pk_mul_f32 v[92:93], v[88:89], v[92:93]
	v_mul_f32_e32 v43, v43, v90
	v_add_f32_e32 v64, 1.0, v64
	v_rcp_f32_e32 v64, v64
	v_mfma_f32_16x16x32_bf16 v[74:77], v[78:81], v[6:9], v[74:77]
	v_mul_f32_e32 v45, v64, v45
	v_lshlrev_b32_e32 v64, 16, v65
	v_mul_f32_e32 v90, 0xbfb8aa3b, v64
	v_exp_f32_e32 v90, v90
	v_mul_f32_e32 v45, v45, v91
	s_nop 2
	v_pk_add_f32 v[74:75], v[82:83], v[74:75]
	v_add_f32_e32 v90, 1.0, v90
	v_rcp_f32_e32 v90, v90
	v_pk_mul_f32 v[74:75], v[86:87], v[74:75]
	v_mul_f32_e32 v64, v90, v64
	v_mul_f32_e32 v90, v64, v92
	v_and_b32_e32 v64, 0xffff0000, v65
	v_mul_f32_e32 v65, 0xbfb8aa3b, v64
	v_exp_f32_e32 v65, v65
	s_nop 0
	v_add_f32_e32 v65, 1.0, v65
	v_rcp_f32_e32 v65, v65
	s_nop 0
	v_mul_f32_e32 v64, v65, v64
	v_mul_f32_e32 v65, v64, v93
	v_cvt_pk_bf16_f32 v64, v43, v45
	v_lshlrev_b32_e32 v43, 16, v62
	v_mul_f32_e32 v45, 0xbfb8aa3b, v43
	v_exp_f32_e32 v45, v45
	v_cvt_pk_bf16_f32 v65, v90, v65
	v_lshl_add_u64 v[90:91], v[28:29], 0, v[60:61]
	global_store_dwordx2 v[90:91], v[64:65], off
	v_add_f32_e32 v45, 1.0, v45
	v_rcp_f32_e32 v45, v45
	v_pk_add_f32 v[64:65], v[84:85], v[76:77]
	v_mul_f32_e32 v43, v45, v43
	v_and_b32_e32 v45, 0xffff0000, v62
	v_mul_f32_e32 v62, 0xbfb8aa3b, v45
	v_exp_f32_e32 v62, v62
	v_mul_f32_e32 v43, v43, v74
	v_pk_mul_f32 v[64:65], v[88:89], v[64:65]
	v_add_f32_e32 v62, 1.0, v62
	v_rcp_f32_e32 v62, v62
	s_nop 0
	v_mul_f32_e32 v45, v62, v45
	v_lshlrev_b32_e32 v62, 16, v63
	v_mul_f32_e32 v74, 0xbfb8aa3b, v62
	v_exp_f32_e32 v74, v74
	v_mul_f32_e32 v45, v45, v75
	v_add_f32_e32 v74, 1.0, v74
	v_rcp_f32_e32 v74, v74
	s_nop 0
	v_mul_f32_e32 v62, v74, v62
	v_mul_f32_e32 v64, v62, v64
	v_and_b32_e32 v62, 0xffff0000, v63
	v_mul_f32_e32 v63, 0xbfb8aa3b, v62
	v_exp_f32_e32 v63, v63
	s_nop 0
	v_add_f32_e32 v63, 1.0, v63
	v_rcp_f32_e32 v63, v63
	s_nop 0
	v_mul_f32_e32 v62, v63, v62
	v_mul_f32_e32 v63, v62, v65
	v_cvt_pk_bf16_f32 v62, v43, v45
	v_cvt_pk_bf16_f32 v63, v64, v63
	v_lshl_add_u64 v[64:65], v[28:29], 0, v[58:59]
	global_store_dwordx2 v[64:65], v[62:63], off
	global_load_dwordx4 v[62:65], v[22:23], off offset:2048
	s_nop 0
	global_load_dwordx4 v[74:77], v[22:23], off offset:2112
	global_load_dwordx4 v[78:81], v[24:25], off offset:64
	global_load_dwordx4 v[82:85], v[26:27], off offset:64
	v_lshlrev_b32_e32 v43, 16, v54
	v_mul_f32_e32 v45, 0xbfb8aa3b, v43
	v_exp_f32_e32 v45, v45
	s_waitcnt vmcnt(0) lgkmcnt(0)
	v_mfma_f32_16x16x32_bf16 v[86:89], v[62:65], v[14:17], 0
	v_add_f32_e32 v45, 1.0, v45
	v_rcp_f32_e32 v45, v45
	v_mfma_f32_16x16x32_bf16 v[86:89], v[74:77], v[18:21], v[86:89]
	v_mul_f32_e32 v43, v45, v43
	v_and_b32_e32 v45, 0xffff0000, v54
	v_mul_f32_e32 v54, 0xbfb8aa3b, v45
	v_exp_f32_e32 v54, v54
	s_nop 3
	v_pk_add_f32 v[86:87], v[78:79], v[86:87]
	v_pk_add_f32 v[88:89], v[80:81], v[88:89]
	v_pk_mul_f32 v[86:87], v[82:83], v[86:87]
	v_add_f32_e32 v54, 1.0, v54
	v_rcp_f32_e32 v54, v54
	v_mul_f32_e32 v43, v43, v86
	v_pk_mul_f32 v[88:89], v[84:85], v[88:89]
	v_mul_f32_e32 v45, v54, v45
	v_lshlrev_b32_e32 v54, 16, v55
	v_mul_f32_e32 v86, 0xbfb8aa3b, v54
	v_exp_f32_e32 v86, v86
	v_and_b32_e32 v55, 0xffff0000, v55
	v_mul_f32_e32 v45, v45, v87
	v_add_f32_e32 v86, 1.0, v86
	v_rcp_f32_e32 v86, v86
	s_nop 0
	v_mul_f32_e32 v54, v86, v54
	v_mul_f32_e32 v86, 0xbfb8aa3b, v55
	v_exp_f32_e32 v86, v86
	v_mul_f32_e32 v54, v54, v88
	v_add_f32_e32 v86, 1.0, v86
	v_rcp_f32_e32 v86, v86
	s_nop 0
	v_mul_f32_e32 v55, v86, v55
	v_cvt_pk_bf16_f32 v86, v43, v45
	v_lshlrev_b32_e32 v43, 16, v56
	v_mul_f32_e32 v45, 0xbfb8aa3b, v43
	v_exp_f32_e32 v45, v45
	v_mul_f32_e32 v55, v55, v89
	v_cvt_pk_bf16_f32 v87, v54, v55
	v_lshl_add_u64 v[54:55], s[36:37], 0, v[60:61]
	v_add_f32_e32 v45, 1.0, v45
	v_rcp_f32_e32 v45, v45
	v_lshl_add_u64 v[60:61], v[54:55], 0, v[0:1]
	global_store_dwordx2 v[60:61], v[86:87], off
	v_mfma_f32_16x16x32_bf16 v[60:63], v[62:65], v[2:5], 0
	v_mul_f32_e32 v43, v45, v43
	v_and_b32_e32 v45, 0xffff0000, v56
	v_mul_f32_e32 v56, 0xbfb8aa3b, v45
	v_exp_f32_e32 v56, v56
	v_mfma_f32_16x16x32_bf16 v[60:63], v[74:77], v[6:9], v[60:63]
	v_add_f32_e32 v56, 1.0, v56
	v_rcp_f32_e32 v56, v56
	s_nop 0
	v_mul_f32_e32 v45, v56, v45
	s_nop 3
	v_pk_add_f32 v[60:61], v[78:79], v[60:61]
	v_lshlrev_b32_e32 v56, 16, v57
	v_pk_mul_f32 v[60:61], v[82:83], v[60:61]
	v_and_b32_e32 v57, 0xffff0000, v57
	v_mul_f32_e32 v43, v43, v60
	v_mul_f32_e32 v60, 0xbfb8aa3b, v56
	v_exp_f32_e32 v60, v60
	v_pk_add_f32 v[62:63], v[80:81], v[62:63]
	v_mul_f32_e32 v45, v45, v61
	v_pk_mul_f32 v[62:63], v[84:85], v[62:63]
	v_add_f32_e32 v60, 1.0, v60
	v_rcp_f32_e32 v60, v60
	s_nop 0
	v_mul_f32_e32 v56, v60, v56
	v_mul_f32_e32 v60, 0xbfb8aa3b, v57
	v_exp_f32_e32 v60, v60
	v_mul_f32_e32 v56, v56, v62
	v_add_f32_e32 v60, 1.0, v60
	v_rcp_f32_e32 v60, v60
	s_nop 0
	v_mul_f32_e32 v57, v60, v57
	v_mul_f32_e32 v57, v57, v63
	v_cvt_pk_bf16_f32 v60, v43, v45
	v_cvt_pk_bf16_f32 v61, v56, v57
	v_lshl_add_u64 v[56:57], s[36:37], 0, v[58:59]
	v_lshl_add_u64 v[58:59], v[56:57], 0, v[0:1]
	global_store_dwordx2 v[58:59], v[60:61], off
	global_load_dwordx4 v[58:61], v[30:31], off
	s_nop 0
	global_load_dwordx4 v[62:65], v[32:33], off
	global_load_dwordx4 v[74:77], v[24:25], off offset:128
	global_load_dwordx4 v[78:81], v[26:27], off offset:128
	v_lshlrev_b32_e32 v43, 16, v52
	v_mul_f32_e32 v45, 0xbfb8aa3b, v43
	v_exp_f32_e32 v45, v45
	s_waitcnt vmcnt(0) lgkmcnt(0)
; __device__ __forceinline__ unsigned cvt_pk_bf16(float lo, float hi) { unsigned r; asm volatile("v_cvt_pk_bf16_f32 %0, %1, %2" : "=v"(r) : "v"(lo), "v"(hi)); return r; }
; __device__ __forceinline__ float bflo(unsigned w) { return __uint_as_float(w << 16); }
; __device__ __forceinline__ float bfhi(unsigned w) { return __uint_as_float(w & 0xffff0000u); }
; __device__ __forceinline__ float siluf(float x) { return x * __builtin_amdgcn_rcpf(1.f + __expf(-x)); }
; #define MFMA16(a, b, c) __builtin_amdgcn_mfma_f32_16x16x32_bf16((a), (b), (c), 0, 0, 0)
; __device__ __forceinline__ void pool_task(int b, int c, int gi, int l, const float* pool_b, const float* pool_s, LAS float* pl, const bf16_t* P, const bf16_t* WPOOL, bf16_t* Z3, int lane) {
;     ...
;     for (int cb = 0; cb < 4; ++cb) {
;         const bf16_t* wp = WPOOL + ((size_t)(l * 4 + gi) * 64 + cb * 16 + fr) * 64 + fq * 8;
;         const bf16x8 w0 = asfrag(ld8(wp)), w1 = asfrag(ld8(wp + 32));
;         const int o4 = gi * 64 + cb * 16 + fq * 4;
;         const f32x4 pb = *(const f32x4*)(pool_b + l * 256 + o4), ps = *(const f32x4*)(pool_s + l * 256 + o4);
; #pragma unroll
;         for (int tb = 0; tb < 2; ++tb) { f32x4 acc = (f32x4){0.f, 0.f, 0.f, 0.f}; acc = MFMA16(w0, bfr[tb][0], acc); acc = MFMA16(w1, bfr[tb][1], acc);
;             const size_t row = (size_t)(rbase + t0 + tb * 16 + fr); const u32x2 g = pgv[cb][tb];
;             f32x4 v = (acc + pb) * ps; v[0] *= siluf(bflo(g.x)); v[1] *= siluf(bfhi(g.x)); v[2] *= siluf(bflo(g.y)); v[3] *= siluf(bfhi(g.y));
;             u32x2 w; w.x = cvt_pk_bf16(v[0], v[1]); w.y = cvt_pk_bf16(v[2], v[3]); *(u32x2*)(Z3 + row * 256 + o4) = w; }
;     }
	v_mfma_f32_16x16x32_bf16 v[82:85], v[58:61], v[14:17], 0
	v_add_f32_e32 v45, 1.0, v45
	v_rcp_f32_e32 v45, v45
	v_mfma_f32_16x16x32_bf16 v[82:85], v[62:65], v[18:21], v[82:85]
	v_mul_f32_e32 v43, v45, v43
	v_and_b32_e32 v45, 0xffff0000, v52
	v_mul_f32_e32 v52, 0xbfb8aa3b, v45
	v_exp_f32_e32 v52, v52
	s_nop 3
	v_pk_add_f32 v[82:83], v[74:75], v[82:83]
	v_pk_add_f32 v[84:85], v[76:77], v[84:85]
	v_pk_mul_f32 v[82:83], v[78:79], v[82:83]
	v_add_f32_e32 v52, 1.0, v52
	v_rcp_f32_e32 v52, v52
	v_mul_f32_e32 v43, v43, v82
	v_pk_mul_f32 v[84:85], v[80:81], v[84:85]
	v_mfma_f32_16x16x32_bf16 v[58:61], v[58:61], v[2:5], 0
	v_mul_f32_e32 v45, v52, v45
	v_lshlrev_b32_e32 v52, 16, v53
	v_mul_f32_e32 v82, 0xbfb8aa3b, v52
	v_exp_f32_e32 v82, v82
	v_mfma_f32_16x16x32_bf16 v[58:61], v[62:65], v[6:9], v[58:61]
	v_mul_f32_e32 v45, v45, v83
	v_add_f32_e32 v82, 1.0, v82
	v_rcp_f32_e32 v82, v82
	s_nop 0
	v_mul_f32_e32 v52, v82, v52
	v_mul_f32_e32 v82, v52, v84
	v_and_b32_e32 v52, 0xffff0000, v53
	v_mul_f32_e32 v53, 0xbfb8aa3b, v52
	v_exp_f32_e32 v53, v53
	v_pk_add_f32 v[58:59], v[74:75], v[58:59]
	v_add_f32_e32 v53, 1.0, v53
	v_rcp_f32_e32 v53, v53
	v_pk_mul_f32 v[58:59], v[78:79], v[58:59]
	v_mul_f32_e32 v52, v53, v52
	v_mul_f32_e32 v53, v52, v85
	v_cvt_pk_bf16_f32 v52, v43, v45
	v_mov_b32_e32 v43, v1
	v_cvt_pk_bf16_f32 v53, v82, v53
	v_lshl_add_u64 v[82:83], v[54:55], 0, v[42:43]
	v_lshlrev_b32_e32 v45, 16, v50
	global_store_dwordx2 v[82:83], v[52:53], off
	v_pk_add_f32 v[52:53], v[76:77], v[60:61]
	v_mul_f32_e32 v60, 0xbfb8aa3b, v45
	v_exp_f32_e32 v60, v60
	v_and_b32_e32 v50, 0xffff0000, v50
	v_pk_mul_f32 v[52:53], v[80:81], v[52:53]
	v_add_f32_e32 v60, 1.0, v60
	v_rcp_f32_e32 v60, v60
	s_nop 0
	v_mul_f32_e32 v45, v60, v45
	v_mul_f32_e32 v45, v45, v58
	v_mul_f32_e32 v58, 0xbfb8aa3b, v50
	v_exp_f32_e32 v58, v58
	s_nop 0
	v_add_f32_e32 v58, 1.0, v58
	v_rcp_f32_e32 v58, v58
	s_nop 0
	v_mul_f32_e32 v50, v58, v50
	v_lshlrev_b32_e32 v58, 16, v51
	v_mul_f32_e32 v50, v50, v59
	v_mul_f32_e32 v59, 0xbfb8aa3b, v58
	v_exp_f32_e32 v59, v59
	v_and_b32_e32 v51, 0xffff0000, v51
	v_cvt_pk_bf16_f32 v50, v45, v50
	v_mov_b32_e32 v45, v1
	v_add_f32_e32 v59, 1.0, v59
	v_rcp_f32_e32 v59, v59
	s_nop 0
	v_mul_f32_e32 v58, v59, v58
	v_mul_f32_e32 v52, v58, v52
	v_mul_f32_e32 v58, 0xbfb8aa3b, v51
	v_exp_f32_e32 v58, v58
	s_nop 0
	v_add_f32_e32 v58, 1.0, v58
	v_rcp_f32_e32 v58, v58
	s_nop 0
	v_mul_f32_e32 v51, v58, v51
	v_mul_f32_e32 v51, v51, v53
	v_cvt_pk_bf16_f32 v51, v52, v51
	v_lshl_add_u64 v[52:53], v[56:57], 0, v[42:43]
	global_store_dwordx2 v[52:53], v[50:51], off
	global_load_dwordx4 v[50:53], v[34:35], off
	s_nop 0
	global_load_dwordx4 v[58:61], v[36:37], off
	global_load_dwordx4 v[62:65], v[24:25], off offset:192
	global_load_dwordx4 v[74:77], v[26:27], off offset:192
	s_waitcnt vmcnt(0) lgkmcnt(0)
	v_mfma_f32_16x16x32_bf16 v[14:17], v[50:53], v[14:17], 0
	v_mfma_f32_16x16x32_bf16 v[2:5], v[50:53], v[2:5], 0
	v_mfma_f32_16x16x32_bf16 v[14:17], v[58:61], v[18:21], v[14:17]
	v_lshlrev_b32_e32 v18, 16, v48
	v_mul_f32_e32 v19, 0xbfb8aa3b, v18
	v_exp_f32_e32 v19, v19
	v_mfma_f32_16x16x32_bf16 v[2:5], v[58:61], v[6:9], v[2:5]
	v_lshlrev_b32_e32 v6, 16, v46
	v_mul_f32_e32 v7, 0xbfb8aa3b, v6
	v_exp_f32_e32 v7, v7
	v_add_f32_e32 v19, 1.0, v19
	v_rcp_f32_e32 v19, v19
	v_pk_add_f32 v[14:15], v[62:63], v[14:15]
	v_add_f32_e32 v7, 1.0, v7
	v_rcp_f32_e32 v7, v7
	v_pk_mul_f32 v[14:15], v[74:75], v[14:15]
	v_mul_f32_e32 v18, v19, v18
	v_pk_add_f32 v[2:3], v[62:63], v[2:3]
	v_mul_f32_e32 v14, v18, v14
	v_and_b32_e32 v18, 0xffff0000, v48
	v_pk_mul_f32 v[2:3], v[74:75], v[2:3]
	v_mul_f32_e32 v6, v7, v6
	v_mul_f32_e32 v19, 0xbfb8aa3b, v18
	v_mul_f32_e32 v2, v6, v2
	v_and_b32_e32 v6, 0xffff0000, v46
	v_exp_f32_e32 v19, v19
	v_mul_f32_e32 v7, 0xbfb8aa3b, v6
	v_exp_f32_e32 v7, v7
	v_pk_add_f32 v[16:17], v[64:65], v[16:17]
	v_add_f32_e32 v19, 1.0, v19
	v_rcp_f32_e32 v19, v19
	v_add_f32_e32 v7, 1.0, v7
	v_rcp_f32_e32 v7, v7
	v_pk_mul_f32 v[16:17], v[76:77], v[16:17]
	v_mul_f32_e32 v18, v19, v18
	v_mul_f32_e32 v15, v18, v15
	v_lshlrev_b32_e32 v18, 16, v49
	v_mul_f32_e32 v6, v7, v6
	v_mul_f32_e32 v19, 0xbfb8aa3b, v18
	v_mul_f32_e32 v3, v6, v3
	v_lshlrev_b32_e32 v6, 16, v47
	v_exp_f32_e32 v19, v19
	v_mul_f32_e32 v7, 0xbfb8aa3b, v6
	v_exp_f32_e32 v7, v7
	v_pk_add_f32 v[4:5], v[64:65], v[4:5]
	v_add_f32_e32 v19, 1.0, v19
	v_rcp_f32_e32 v19, v19
	v_add_f32_e32 v7, 1.0, v7
	v_rcp_f32_e32 v7, v7
	v_pk_mul_f32 v[4:5], v[76:77], v[4:5]
	v_mul_f32_e32 v18, v19, v18
	v_mul_f32_e32 v16, v18, v16
	v_and_b32_e32 v18, 0xffff0000, v49
	v_mul_f32_e32 v6, v7, v6
	v_mul_f32_e32 v19, 0xbfb8aa3b, v18
	v_mul_f32_e32 v4, v6, v4
	v_and_b32_e32 v6, 0xffff0000, v47
	v_exp_f32_e32 v19, v19
	v_mul_f32_e32 v7, 0xbfb8aa3b, v6
	v_exp_f32_e32 v7, v7
	v_cvt_pk_bf16_f32 v14, v14, v15
	v_add_f32_e32 v19, 1.0, v19
	v_rcp_f32_e32 v19, v19
	v_add_f32_e32 v7, 1.0, v7
	v_rcp_f32_e32 v7, v7
	v_mul_f32_e32 v18, v19, v18
	v_mul_f32_e32 v17, v18, v17
	v_mul_f32_e32 v6, v7, v6
	v_cvt_pk_bf16_f32 v15, v16, v17
	v_lshl_add_u64 v[16:17], v[54:55], 0, v[44:45]
	v_mul_f32_e32 v5, v6, v5
	global_store_dwordx2 v[16:17], v[14:15], off
	v_cvt_pk_bf16_f32 v2, v2, v3
	v_cvt_pk_bf16_f32 v3, v4, v5
	v_lshl_add_u64 v[4:5], v[56:57], 0, v[44:45]
	global_store_dwordx2 v[4:5], v[2:3], off
	s_waitcnt lgkmcnt(0)
	s_cbranch_scc1 .LBB0_843

; __device__ __forceinline__ bf16_t tobf(float f) { return (bf16_t)(cvt_pk_bf16(f, 0.f) & 0xffffu); }
; __global__ void __launch_bounds__(512, 2) fwd_kernel(KArgs a) {
;     ...
;             if (tid < 64) for (int ch = bid * 64 + tid; ch < HB * 16 * 2 * 64; ch += G * 64) {
;                 const int p = ch & 63, d = (ch >> 6) & 1, g = (ch >> 7) & 15, b = ch >> 11;
;                 const float* aw = POW + ((size_t)(((l * 2 + d) * 16 + g) * 33 + 32) * 64 + p) * 2; const float ar = aw[0], ai = aw[1];
;                 float hr = 0.f, hi = 0.f;
;                 for (int n0 = 0; n0 < NCH; n0 += 8) { float sr[8], si[8];
; #pragma unroll
;                     for (int k = 0; k < 8; ++k) { const int n = n0 + k, c = d == 0 ? n : (n < 8 ? 7 - n : 79 - n); const size_t idx = ((size_t)(b * NCH + c) * 16 + g) * 256 + d * 128 + p; sr[k] = S5S[idx]; si[k] = S5S[idx + 64]; }
; #pragma unroll
;                     for (int k = 0; k < 8; ++k) { const int n = n0 + k, c = d == 0 ? n : (n < 8 ? 7 - n : 79 - n); const size_t idx = ((size_t)(b * NCH + c) * 16 + g) * 256 + d * 128 + p;
;                         S5H[idx] = tobf(hr); S5H[idx + 64] = tobf(hi);
;                         const float nr = ar * hr - ai * hi + sr[k], ni = ar * hi + ai * hr + si[k]; hr = nr; hi = ni; } }
.LBB0_997:
	v_bfe_u32 v14, v40, 6, 1
	v_bfe_u32 v8, v40, 7, 4
	v_lshlrev_b32_e32 v0, 4, v14
	v_or3_b32 v0, v0, s18, v8
	v_mul_u32_u24_e32 v0, 0x840, v0
	v_or_b32_e32 v0, v0, v2
	v_lshl_add_u32 v0, v0, 1, v207
	v_lshl_add_u64 v[4:5], v[0:1], 2, s[38:39]
	global_load_dwordx2 v[4:5], v[4:5], off
	v_ashrrev_i32_e32 v0, 11, v40
	v_mul_i32_i24_e32 v41, 0x48, v0
	v_lshlrev_b32_e32 v0, 10, v8
	v_lshl_add_u64 v[6:7], s[40:41], 0, v[0:1]
	v_lshlrev_b32_e32 v0, 9, v14
	v_lshl_add_u64 v[6:7], v[6:7], 0, v[0:1]
	v_lshlrev_b32_e32 v0, 2, v2
	v_lshl_add_u64 v[6:7], v[6:7], 0, v[0:1]
	v_lshlrev_b32_e32 v0, 9, v8
	v_lshl_add_u64 v[8:9], s[42:43], 0, v[0:1]
	v_lshlrev_b32_e32 v0, 8, v14
	v_mov_b32_e32 v16, 0
	v_lshl_add_u64 v[8:9], v[8:9], 0, v[0:1]
	v_lshlrev_b32_e32 v0, 1, v2
	s_mov_b32 s1, 0
	s_mov_b32 s6, 0
	v_cmp_eq_u32_e32 vcc, 0, v14
	v_lshl_add_u64 v[8:9], v[8:9], 0, v[0:1]
	v_mov_b32_e32 v17, v16
	s_waitcnt vmcnt(0) lgkmcnt(0)
	v_pk_mov_b32 v[14:15], v[4:5], v[4:5] op_sel:[1,0]
.LBB0_998:
	s_cmp_eq_u32 s1, 0
	s_cselect_b32 s7, 7, 0x4f
	s_add_i32 s7, s7, s1
	v_mov_b32_e32 v0, s7
	v_mov_b32_e32 v18, s6
	v_cndmask_b32_e32 v0, v0, v18, vcc
	v_add_u32_e32 v48, v0, v41
	v_ashrrev_i32_e32 v49, 31, v48
	v_lshlrev_b64 v[18:19], 14, v[48:49]
	v_lshl_add_u64 v[18:19], v[6:7], 0, v[18:19]
	s_or_b32 s14, s6, 1
	s_add_i32 s15, s7, -1
	global_load_dword v52, v[18:19], off
	global_load_dword v45, v[18:19], off offset:256
	v_mov_b32_e32 v0, s15
	v_mov_b32_e32 v18, s14
	v_cndmask_b32_e32 v0, v0, v18, vcc
	v_add_u32_e32 v32, v0, v41
	v_ashrrev_i32_e32 v33, 31, v32
	v_lshlrev_b64 v[18:19], 14, v[32:33]
	v_lshl_add_u64 v[18:19], v[6:7], 0, v[18:19]
	s_or_b32 s14, s6, 2
	s_add_i32 s15, s7, -2
	global_load_dword v24, v[18:19], off
	global_load_dword v25, v[18:19], off offset:256
	v_mov_b32_e32 v0, s15
	v_mov_b32_e32 v18, s14
	v_cndmask_b32_e32 v0, v0, v18, vcc
	v_add_u32_e32 v38, v0, v41
	v_ashrrev_i32_e32 v39, 31, v38
	v_lshlrev_b64 v[18:19], 14, v[38:39]
	v_lshl_add_u64 v[18:19], v[6:7], 0, v[18:19]
	s_or_b32 s14, s6, 3
	s_add_i32 s15, s7, -3
	global_load_dword v47, v[18:19], off
	global_load_dword v43, v[18:19], off offset:256
	v_mov_b32_e32 v0, s15
	v_mov_b32_e32 v18, s14
	v_cndmask_b32_e32 v0, v0, v18, vcc
	v_add_u32_e32 v30, v0, v41
	v_ashrrev_i32_e32 v31, 31, v30
	v_lshlrev_b64 v[18:19], 14, v[30:31]
	v_lshl_add_u64 v[18:19], v[6:7], 0, v[18:19]
	s_or_b32 s14, s6, 4
	s_add_i32 s15, s7, -4
	global_load_dword v22, v[18:19], off
	global_load_dword v23, v[18:19], off offset:256
	v_mov_b32_e32 v0, s15
	v_mov_b32_e32 v18, s14
	v_cndmask_b32_e32 v0, v0, v18, vcc
	v_add_u32_e32 v36, v0, v41
	v_ashrrev_i32_e32 v37, 31, v36
	v_lshlrev_b64 v[18:19], 14, v[36:37]
	v_lshl_add_u64 v[18:19], v[6:7], 0, v[18:19]
	s_or_b32 s14, s6, 5
	s_add_i32 s15, s7, -5
	global_load_dword v46, v[18:19], off
	global_load_dword v42, v[18:19], off offset:256
	v_mov_b32_e32 v0, s15
	v_mov_b32_e32 v18, s14
	v_cndmask_b32_e32 v0, v0, v18, vcc
	v_add_u32_e32 v28, v0, v41
	v_ashrrev_i32_e32 v29, 31, v28
	v_lshlrev_b64 v[18:19], 14, v[28:29]
	v_lshl_add_u64 v[20:21], v[6:7], 0, v[18:19]
	s_or_b32 s14, s6, 6
	s_add_i32 s15, s7, -6
	global_load_dword v18, v[20:21], off
	global_load_dword v19, v[20:21], off offset:256
	v_mov_b32_e32 v0, s15
	v_mov_b32_e32 v20, s14
	v_cndmask_b32_e32 v0, v0, v20, vcc
	v_add_u32_e32 v34, v0, v41
	v_ashrrev_i32_e32 v35, 31, v34
	v_lshlrev_b64 v[20:21], 14, v[34:35]
	v_lshl_add_u64 v[20:21], v[6:7], 0, v[20:21]
	s_or_b32 s14, s6, 7
	s_add_i32 s7, s7, -7
	global_load_dword v44, v[20:21], off
	global_load_dword v0, v[20:21], off offset:256
	v_mov_b32_e32 v20, s7
	v_mov_b32_e32 v21, s14
	v_cndmask_b32_e32 v20, v20, v21, vcc
	v_add_u32_e32 v26, v20, v41
	v_ashrrev_i32_e32 v27, 31, v26
	v_lshlrev_b64 v[20:21], 14, v[26:27]
	v_lshl_add_u64 v[50:51], v[6:7], 0, v[20:21]
	global_load_dword v20, v[50:51], off
	global_load_dword v21, v[50:51], off offset:256
	v_lshlrev_b64 v[48:49], 13, v[48:49]
	v_cvt_pk_bf16_f32 v50, v16, v1
	v_lshl_add_u64 v[48:49], v[8:9], 0, v[48:49]
	global_store_short v[48:49], v50, off
	v_cvt_pk_bf16_f32 v50, v17, v1
	global_store_short v[48:49], v50, off offset:128
	v_pk_mul_f32 v[48:49], v[4:5], v[16:17]
	v_pk_mul_f32 v[16:17], v[4:5], v[16:17] op_sel:[0,1] op_sel_hi:[1,0]
	v_sub_f32_e32 v48, v48, v49
	v_lshlrev_b64 v[32:33], 13, v[32:33]
	s_waitcnt vmcnt(0) lgkmcnt(0)
; __device__ __forceinline__ bf16_t tobf(float f) { return (bf16_t)(cvt_pk_bf16(f, 0.f) & 0xffffu); }
; __global__ void __launch_bounds__(512, 2) fwd_kernel(KArgs a) {
;     ...
;                 for (int n0 = 0; n0 < NCH; n0 += 8) { float sr[8], si[8];
; #pragma unroll
;                     for (int k = 0; k < 8; ++k) { const int n = n0 + k, c = d == 0 ? n : (n < 8 ? 7 - n : 79 - n); const size_t idx = ((size_t)(b * NCH + c) * 16 + g) * 256 + d * 128 + p; sr[k] = S5S[idx]; si[k] = S5S[idx + 64]; }
; #pragma unroll
;                     for (int k = 0; k < 8; ++k) { const int n = n0 + k, c = d == 0 ? n : (n < 8 ? 7 - n : 79 - n); const size_t idx = ((size_t)(b * NCH + c) * 16 + g) * 256 + d * 128 + p;
;                         S5H[idx] = tobf(hr); S5H[idx + 64] = tobf(hi);
;                         const float nr = ar * hr - ai * hi + sr[k], ni = ar * hi + ai * hr + si[k]; hr = nr; hi = ni; } }
	v_add_f32_e32 v48, v48, v52
	v_add_f32_e32 v16, v16, v17
	v_cvt_pk_bf16_f32 v17, v48, v1
	v_lshl_add_u64 v[32:33], v[8:9], 0, v[32:33]
	v_add_f32_e32 v16, v16, v45
	global_store_short v[32:33], v17, off
	v_cvt_pk_bf16_f32 v17, v16, v1
	global_store_short v[32:33], v17, off offset:128
	v_pk_mul_f32 v[16:17], v[14:15], v[16:17] op_sel_hi:[1,0]
	v_lshlrev_b64 v[32:33], 13, v[38:39]
	v_pk_fma_f32 v[38:39], v[4:5], v[48:49], v[16:17] neg_lo:[0,0,1] neg_hi:[0,0,1]
	v_pk_fma_f32 v[16:17], v[4:5], v[48:49], v[16:17] op_sel_hi:[1,0,1]
	v_lshl_add_u64 v[32:33], v[8:9], 0, v[32:33]
	v_mov_b32_e32 v39, v17
	v_pk_add_f32 v[16:17], v[38:39], v[24:25]
	v_lshlrev_b64 v[30:31], 13, v[30:31]
	v_cvt_pk_bf16_f32 v24, v16, v1
	global_store_short v[32:33], v24, off
	v_cvt_pk_bf16_f32 v24, v17, v1
	global_store_short v[32:33], v24, off offset:128
	v_pk_mul_f32 v[24:25], v[4:5], v[16:17]
	v_pk_mul_f32 v[16:17], v[4:5], v[16:17] op_sel:[0,1] op_sel_hi:[1,0]
	v_sub_f32_e32 v24, v24, v25
	v_add_f32_e32 v24, v24, v47
	v_add_f32_e32 v16, v16, v17
	v_cvt_pk_bf16_f32 v17, v24, v1
	v_lshl_add_u64 v[30:31], v[8:9], 0, v[30:31]
	v_add_f32_e32 v16, v16, v43
	global_store_short v[30:31], v17, off
	v_cvt_pk_bf16_f32 v17, v16, v1
	global_store_short v[30:31], v17, off offset:128
	v_pk_mul_f32 v[16:17], v[14:15], v[16:17] op_sel_hi:[1,0]
	v_lshlrev_b64 v[30:31], 13, v[36:37]
	v_pk_fma_f32 v[32:33], v[4:5], v[24:25], v[16:17] neg_lo:[0,0,1] neg_hi:[0,0,1]
	v_pk_fma_f32 v[16:17], v[4:5], v[24:25], v[16:17] op_sel_hi:[1,0,1]
	v_lshl_add_u64 v[30:31], v[8:9], 0, v[30:31]
	v_mov_b32_e32 v33, v17
	v_pk_add_f32 v[16:17], v[32:33], v[22:23]
	v_lshlrev_b64 v[24:25], 13, v[28:29]
	v_cvt_pk_bf16_f32 v22, v16, v1
	global_store_short v[30:31], v22, off
	v_cvt_pk_bf16_f32 v22, v17, v1
	global_store_short v[30:31], v22, off offset:128
	v_pk_mul_f32 v[22:23], v[4:5], v[16:17]
	v_pk_mul_f32 v[16:17], v[4:5], v[16:17] op_sel:[0,1] op_sel_hi:[1,0]
	v_sub_f32_e32 v22, v22, v23
	v_add_f32_e32 v22, v22, v46
	v_add_f32_e32 v16, v16, v17
	v_cvt_pk_bf16_f32 v17, v22, v1
	v_lshl_add_u64 v[24:25], v[8:9], 0, v[24:25]
	v_add_f32_e32 v16, v16, v42
	global_store_short v[24:25], v17, off
	v_cvt_pk_bf16_f32 v17, v16, v1
	global_store_short v[24:25], v17, off offset:128
	v_pk_mul_f32 v[16:17], v[14:15], v[16:17] op_sel_hi:[1,0]
	v_lshlrev_b64 v[24:25], 13, v[34:35]
	v_pk_fma_f32 v[28:29], v[4:5], v[22:23], v[16:17] neg_lo:[0,0,1] neg_hi:[0,0,1]
	v_pk_fma_f32 v[16:17], v[4:5], v[22:23], v[16:17] op_sel_hi:[1,0,1]
	v_lshl_add_u64 v[24:25], v[8:9], 0, v[24:25]
	v_mov_b32_e32 v29, v17
	v_pk_add_f32 v[16:17], v[28:29], v[18:19]
	s_add_i32 s7, s6, 8
	v_cvt_pk_bf16_f32 v18, v16, v1
	global_store_short v[24:25], v18, off
	v_cvt_pk_bf16_f32 v18, v17, v1
	global_store_short v[24:25], v18, off offset:128
	v_pk_mul_f32 v[18:19], v[4:5], v[16:17]
	v_pk_mul_f32 v[16:17], v[4:5], v[16:17] op_sel:[0,1] op_sel_hi:[1,0]
	v_sub_f32_e32 v18, v18, v19
	v_add_f32_e32 v16, v16, v17
	v_add_f32_e32 v0, v16, v0
	v_lshlrev_b64 v[16:17], 13, v[26:27]
	v_add_f32_e32 v18, v18, v44
	v_cvt_pk_bf16_f32 v19, v18, v1
	v_lshl_add_u64 v[16:17], v[8:9], 0, v[16:17]
	global_store_short v[16:17], v19, off
	v_cvt_pk_bf16_f32 v19, v0, v1
	global_store_short v[16:17], v19, off offset:128
	v_pk_mul_f32 v[16:17], v[14:15], v[0:1] op_sel_hi:[1,0]
	s_add_i32 s1, s1, -8
	v_pk_fma_f32 v[22:23], v[4:5], v[18:19], v[16:17] neg_lo:[0,0,1] neg_hi:[0,0,1]
	v_pk_fma_f32 v[16:17], v[4:5], v[18:19], v[16:17] op_sel_hi:[1,0,1]
	s_cmp_gt_u32 s6, 63
	v_mov_b32_e32 v23, v17
	v_pk_add_f32 v[16:17], v[22:23], v[20:21]
	s_mov_b32 s6, s7
	s_cbranch_scc0 .LBB0_998
	v_add_u32_e32 v40, s75, v40
	v_cmp_lt_i32_e32 vcc, s49, v40
	s_or_b64 s[44:45], vcc, s[44:45]
	s_andn2_b64 exec, exec, s[44:45]
	s_cbranch_execnz .LBB0_997

; __global__ void __launch_bounds__(512, 2) fwd_kernel(KArgs a) {
;     ...
;             if (tid >= 64 && tid < 80) for (int ch = bid * 16 + (tid - 64); ch < HB * 2 * 256; ch += G * 16) {
;                 const int cn = ch & 255, d = (ch >> 8) & 1, b = ch >> 9; float h = 0.f;
;                 for (int n0 = 0; n0 < NCH; n0 += 8) { float la[8], lb[8];
; #pragma unroll
;                     for (int k = 0; k < 8; ++k) { const int n = n0 + k, c = d == 0 ? n : (n < 8 ? 7 - n : 79 - n); const size_t idx = ((size_t)(b * NCH + c) * 2 + d) * 256 + cn; la[k] = LRA[idx]; lb[k] = LRB[idx]; }
; #pragma unroll
;                     for (int k = 0; k < 8; ++k) { const int n = n0 + k, c = d == 0 ? n : (n < 8 ? 7 - n : 79 - n); const size_t idx = ((size_t)(b * NCH + c) * 2 + d) * 256 + cn; LRH[idx] = h; h = la[k] * h + lb[k]; } }
.LBB0_1003:
	v_ashrrev_i32_e32 v2, 9, v22
	v_bfe_i32 v0, v22, 8, 1
	v_mul_i32_i24_e32 v23, 0x48, v2
	v_and_or_b32 v2, v0, 7, v23
	v_and_b32_e32 v4, 0x1ff, v22
	v_ashrrev_i32_e32 v3, 31, v2
	v_lshlrev_b32_e32 v0, 2, v4
	v_lshlrev_b64 v[6:7], 11, v[2:3]
	v_bfe_u32 v5, v22, 8, 1
	v_or_b32_e32 v2, v6, v0
	v_mov_b32_e32 v3, v7
	v_cmp_eq_u32_e32 vcc, 0, v5
	v_lshl_add_u64 v[8:9], s[38:39], 0, v[2:3]
	v_lshl_add_u64 v[2:3], s[40:41], 0, v[2:3]
	global_load_dword v30, v[8:9], off
	global_load_dword v31, v[2:3], off
	v_cndmask_b32_e64 v2, 6, 1, vcc
	v_or_b32_e32 v2, v2, v23
	v_ashrrev_i32_e32 v3, 31, v2
	v_lshlrev_b64 v[8:9], 11, v[2:3]
	v_or_b32_e32 v2, v8, v0
	v_mov_b32_e32 v3, v9
	v_lshl_add_u64 v[14:15], s[38:39], 0, v[2:3]
	v_lshl_add_u64 v[2:3], s[40:41], 0, v[2:3]
	global_load_dword v32, v[14:15], off
	global_load_dword v33, v[2:3], off
	v_cndmask_b32_e64 v2, 5, 2, vcc
	v_or_b32_e32 v2, v2, v23
	v_ashrrev_i32_e32 v3, 31, v2
	v_lshlrev_b64 v[14:15], 11, v[2:3]
	v_or_b32_e32 v2, v14, v0
	v_mov_b32_e32 v3, v15
	v_lshl_add_u64 v[16:17], s[38:39], 0, v[2:3]
	v_lshl_add_u64 v[2:3], s[40:41], 0, v[2:3]
	global_load_dword v34, v[16:17], off
	global_load_dword v35, v[2:3], off
	v_or_b32_e32 v2, v5, v23
	v_add_u32_e32 v2, 3, v2
	v_ashrrev_i32_e32 v3, 31, v2
	v_lshlrev_b64 v[16:17], 11, v[2:3]
	v_or_b32_e32 v2, v16, v0
	v_mov_b32_e32 v3, v17
	v_lshl_add_u64 v[18:19], s[38:39], 0, v[2:3]
	v_lshl_add_u64 v[2:3], s[40:41], 0, v[2:3]
	global_load_dword v36, v[18:19], off
	global_load_dword v37, v[2:3], off
	v_sub_u32_e32 v2, v23, v5
	v_ashrrev_i32_e32 v3, 31, v2
	v_lshlrev_b64 v[2:3], 11, v[2:3]
	s_mov_b64 s[6:7], 0x2000
	v_lshl_add_u64 v[18:19], v[2:3], 0, s[6:7]
	v_or_b32_e32 v2, v18, v0
	v_mov_b32_e32 v3, v19
	v_lshl_add_u64 v[20:21], s[38:39], 0, v[2:3]
	v_lshl_add_u64 v[2:3], s[40:41], 0, v[2:3]
	global_load_dword v38, v[20:21], off
	global_load_dword v39, v[2:3], off
	v_cndmask_b32_e64 v2, 2, 5, vcc
	v_or_b32_e32 v2, v2, v23
	v_ashrrev_i32_e32 v3, 31, v2
	v_lshlrev_b64 v[20:21], 11, v[2:3]
	v_or_b32_e32 v2, v20, v0
	v_mov_b32_e32 v3, v21
	v_lshl_add_u64 v[24:25], s[38:39], 0, v[2:3]
	v_lshl_add_u64 v[2:3], s[40:41], 0, v[2:3]
	global_load_dword v40, v[24:25], off
	global_load_dword v41, v[2:3], off
	v_cndmask_b32_e64 v2, 1, 6, vcc
	v_or_b32_e32 v2, v2, v23
	v_ashrrev_i32_e32 v3, 31, v2
	v_lshlrev_b64 v[26:27], 11, v[2:3]
	v_or_b32_e32 v2, v26, v0
	v_mov_b32_e32 v3, v27
	v_lshl_add_u64 v[24:25], s[38:39], 0, v[2:3]
	v_lshl_add_u64 v[2:3], s[40:41], 0, v[2:3]
	global_load_dword v42, v[24:25], off
	global_load_dword v43, v[2:3], off
	v_cndmask_b32_e64 v2, 0, 7, vcc
	v_or_b32_e32 v2, v2, v23
	v_ashrrev_i32_e32 v3, 31, v2
	v_lshlrev_b64 v[28:29], 11, v[2:3]
	v_or_b32_e32 v2, v28, v0
	v_mov_b32_e32 v3, v29
	v_lshl_add_u64 v[24:25], s[38:39], 0, v[2:3]
	v_lshl_add_u64 v[2:3], s[40:41], 0, v[2:3]
	global_load_dword v25, v[24:25], off
	v_lshlrev_b32_e32 v0, 10, v5
	global_load_dword v24, v[2:3], off
	v_lshl_add_u64 v[2:3], s[4:5], 0, v[0:1]
	v_lshlrev_b32_sdwa v0, v208, v22 dst_sel:DWORD dst_unused:UNUSED_PAD src0_sel:DWORD src1_sel:BYTE_0
	v_lshl_add_u64 v[2:3], v[2:3], 0, v[0:1]
	v_lshl_add_u64 v[6:7], v[2:3], 0, v[6:7]
	global_store_dword v[6:7], v1, off
	v_lshl_add_u64 v[6:7], v[2:3], 0, v[8:9]
	s_mov_b32 s6, 8
	s_waitcnt vmcnt(0) lgkmcnt(0)
	v_fmac_f32_e32 v31, 0, v30
	global_store_dword v[6:7], v31, off
	v_lshl_add_u64 v[6:7], v[2:3], 0, v[14:15]
	s_movk_i32 s1, 0x47
	v_lshlrev_b32_e32 v0, 2, v4
	v_fmac_f32_e32 v33, v31, v32
	global_store_dword v[6:7], v33, off
	v_lshl_add_u64 v[6:7], v[2:3], 0, v[16:17]
	v_fmac_f32_e32 v35, v33, v34
	global_store_dword v[6:7], v35, off
	v_lshl_add_u64 v[6:7], v[2:3], 0, v[18:19]
	v_fmac_f32_e32 v37, v35, v36
	global_store_dword v[6:7], v37, off
	v_lshl_add_u64 v[6:7], v[2:3], 0, v[20:21]
	v_fmac_f32_e32 v39, v37, v38
	global_store_dword v[6:7], v39, off
	v_lshl_add_u64 v[6:7], v[2:3], 0, v[26:27]
	v_fmac_f32_e32 v41, v39, v40
	global_store_dword v[6:7], v41, off
	v_lshl_add_u64 v[6:7], v[2:3], 0, v[28:29]
	v_fmac_f32_e32 v43, v41, v42
	global_store_dword v[6:7], v43, off
	v_fmac_f32_e32 v24, v43, v25
; __global__ void __launch_bounds__(512, 2) fwd_kernel(KArgs a) {
;     ...
;                 for (int n0 = 0; n0 < NCH; n0 += 8) { float la[8], lb[8];
; #pragma unroll
;                     for (int k = 0; k < 8; ++k) { const int n = n0 + k, c = d == 0 ? n : (n < 8 ? 7 - n : 79 - n); const size_t idx = ((size_t)(b * NCH + c) * 2 + d) * 256 + cn; la[k] = LRA[idx]; lb[k] = LRB[idx]; }
; #pragma unroll
;                     for (int k = 0; k < 8; ++k) { const int n = n0 + k, c = d == 0 ? n : (n < 8 ? 7 - n : 79 - n); const size_t idx = ((size_t)(b * NCH + c) * 2 + d) * 256 + cn; LRH[idx] = h; h = la[k] * h + lb[k]; } }
.LBB0_1004:
	v_mov_b32_e32 v4, s1
	v_mov_b32_e32 v5, s6
	v_cndmask_b32_e32 v4, v4, v5, vcc
	v_add_u32_e32 v4, v4, v23
	v_ashrrev_i32_e32 v5, 31, v4
	v_lshlrev_b64 v[4:5], 11, v[4:5]
	v_or_b32_e32 v6, v4, v0
	v_mov_b32_e32 v7, v5
	v_lshl_add_u64 v[8:9], s[38:39], 0, v[6:7]
	v_lshl_add_u64 v[6:7], s[40:41], 0, v[6:7]
	s_add_i32 s7, s1, -1
	s_add_i32 s14, s6, 1
	global_load_dword v26, v[8:9], off
	global_load_dword v25, v[6:7], off
	v_mov_b32_e32 v6, s7
	v_mov_b32_e32 v7, s14
	v_cndmask_b32_e32 v6, v6, v7, vcc
	v_add_u32_e32 v6, v6, v23
	v_ashrrev_i32_e32 v7, 31, v6
	v_lshlrev_b64 v[6:7], 11, v[6:7]
	v_or_b32_e32 v8, v6, v0
	v_mov_b32_e32 v9, v7
	v_lshl_add_u64 v[14:15], s[38:39], 0, v[8:9]
	v_lshl_add_u64 v[8:9], s[40:41], 0, v[8:9]
	s_add_i32 s7, s1, -2
	s_add_i32 s14, s6, 2
	global_load_dword v28, v[14:15], off
	global_load_dword v27, v[8:9], off
	v_mov_b32_e32 v8, s7
	v_mov_b32_e32 v9, s14
	v_cndmask_b32_e32 v8, v8, v9, vcc
	v_add_u32_e32 v8, v8, v23
	v_ashrrev_i32_e32 v9, 31, v8
	v_lshlrev_b64 v[8:9], 11, v[8:9]
	v_or_b32_e32 v14, v8, v0
	v_mov_b32_e32 v15, v9
	v_lshl_add_u64 v[16:17], s[38:39], 0, v[14:15]
	v_lshl_add_u64 v[14:15], s[40:41], 0, v[14:15]
	s_add_i32 s7, s1, -3
	s_add_i32 s14, s6, 3
	global_load_dword v30, v[16:17], off
	global_load_dword v29, v[14:15], off
	v_mov_b32_e32 v14, s7
	v_mov_b32_e32 v15, s14
	v_cndmask_b32_e32 v14, v14, v15, vcc
	v_add_u32_e32 v14, v14, v23
	v_ashrrev_i32_e32 v15, 31, v14
	v_lshlrev_b64 v[14:15], 11, v[14:15]
	v_or_b32_e32 v16, v14, v0
	v_mov_b32_e32 v17, v15
	v_lshl_add_u64 v[18:19], s[38:39], 0, v[16:17]
	v_lshl_add_u64 v[16:17], s[40:41], 0, v[16:17]
	s_add_i32 s7, s1, -4
	s_add_i32 s14, s6, 4
	global_load_dword v32, v[18:19], off
	global_load_dword v31, v[16:17], off
	v_mov_b32_e32 v16, s7
	v_mov_b32_e32 v17, s14
	v_cndmask_b32_e32 v16, v16, v17, vcc
	v_add_u32_e32 v16, v16, v23
	v_ashrrev_i32_e32 v17, 31, v16
	v_lshlrev_b64 v[16:17], 11, v[16:17]
	v_or_b32_e32 v18, v16, v0
	v_mov_b32_e32 v19, v17
	v_lshl_add_u64 v[20:21], s[38:39], 0, v[18:19]
	v_lshl_add_u64 v[18:19], s[40:41], 0, v[18:19]
	s_add_i32 s7, s1, -5
	s_add_i32 s14, s6, 5
	global_load_dword v34, v[20:21], off
	global_load_dword v33, v[18:19], off
	v_mov_b32_e32 v18, s7
	v_mov_b32_e32 v19, s14
	v_cndmask_b32_e32 v18, v18, v19, vcc
	v_add_u32_e32 v18, v18, v23
	v_ashrrev_i32_e32 v19, 31, v18
	v_lshlrev_b64 v[18:19], 11, v[18:19]
	v_or_b32_e32 v20, v18, v0
	v_mov_b32_e32 v21, v19
	v_lshl_add_u64 v[36:37], s[38:39], 0, v[20:21]
	v_lshl_add_u64 v[20:21], s[40:41], 0, v[20:21]
	s_add_i32 s7, s1, -6
	s_add_i32 s14, s6, 6
	global_load_dword v35, v[36:37], off
	global_load_dword v42, v[20:21], off
	v_mov_b32_e32 v20, s7
	v_mov_b32_e32 v21, s14
	v_cndmask_b32_e32 v20, v20, v21, vcc
	v_add_u32_e32 v20, v20, v23
	v_ashrrev_i32_e32 v21, 31, v20
	v_lshlrev_b64 v[20:21], 11, v[20:21]
	v_or_b32_e32 v36, v20, v0
	v_mov_b32_e32 v37, v21
	v_lshl_add_u64 v[38:39], s[38:39], 0, v[36:37]
	v_lshl_add_u64 v[36:37], s[40:41], 0, v[36:37]
	s_add_i32 s7, s1, -7
	s_add_i32 s14, s6, 7
	global_load_dword v43, v[38:39], off
	global_load_dword v44, v[36:37], off
	v_mov_b32_e32 v36, s7
	v_mov_b32_e32 v37, s14
	v_cndmask_b32_e32 v36, v36, v37, vcc
	v_add_u32_e32 v36, v36, v23
	v_ashrrev_i32_e32 v37, 31, v36
	v_lshlrev_b64 v[36:37], 11, v[36:37]
	v_or_b32_e32 v38, v36, v0
	v_mov_b32_e32 v39, v37
	v_lshl_add_u64 v[40:41], s[38:39], 0, v[38:39]
	v_lshl_add_u64 v[38:39], s[40:41], 0, v[38:39]
	global_load_dword v40, v[40:41], off
	s_waitcnt vmcnt(0) lgkmcnt(0)
	v_fmac_f32_e32 v25, v24, v26
	global_load_dword v38, v[38:39], off
	v_lshl_add_u64 v[4:5], v[2:3], 0, v[4:5]
	v_fmac_f32_e32 v27, v25, v28
	global_store_dword v[4:5], v24, off
	v_lshl_add_u64 v[4:5], v[2:3], 0, v[6:7]
	global_store_dword v[4:5], v25, off
	v_lshl_add_u64 v[4:5], v[2:3], 0, v[8:9]
	global_store_dword v[4:5], v27, off
	v_lshl_add_u64 v[4:5], v[2:3], 0, v[14:15]
	s_add_i32 s1, s1, -8
	s_add_i32 s7, s6, 8
	v_fmac_f32_e32 v29, v27, v30
	global_store_dword v[4:5], v29, off
	v_lshl_add_u64 v[4:5], v[2:3], 0, v[16:17]
	s_cmp_gt_u32 s6, 63
	s_mov_b32 s6, s7
	v_fmac_f32_e32 v31, v29, v32
	global_store_dword v[4:5], v31, off
	v_lshl_add_u64 v[4:5], v[2:3], 0, v[18:19]
	v_fmac_f32_e32 v33, v31, v34
	global_store_dword v[4:5], v33, off
	v_lshl_add_u64 v[4:5], v[2:3], 0, v[20:21]
	v_fmac_f32_e32 v42, v33, v35
	global_store_dword v[4:5], v42, off
	v_lshl_add_u64 v[4:5], v[2:3], 0, v[36:37]
	v_fmac_f32_e32 v44, v42, v43
	global_store_dword v[4:5], v44, off
	s_waitcnt vmcnt(0) lgkmcnt(0)
	v_fmac_f32_e32 v38, v44, v40
	v_mov_b32_e32 v24, v38
	s_cbranch_scc0 .LBB0_1004
	v_add_u32_e32 v22, s93, v22
	s_movk_i32 s1, 0xfff
	v_cmp_lt_i32_e32 vcc, s1, v22
	s_or_b64 s[42:43], vcc, s[42:43]
	s_andn2_b64 exec, exec, s[42:43]
	s_cbranch_execnz .LBB0_1003

; __device__ __forceinline__ unsigned cvt_pk_bf16(float lo, float hi) { unsigned r; asm volatile("v_cvt_pk_bf16_f32 %0, %1, %2" : "=v"(r) : "v"(lo), "v"(hi)); return r; }
; __device__ __forceinline__ float bflo(unsigned w) { return __uint_as_float(w << 16); }
; __device__ __forceinline__ float bfhi(unsigned w) { return __uint_as_float(w & 0xffff0000u); }
; __device__ __forceinline__ float siluf(float x) { return x * __builtin_amdgcn_rcpf(1.f + __expf(-x)); }
; __device__ __forceinline__ void attn_unit(LAS unsigned char* lds, const bf16_t* QB, const bf16_t* KB, const bf16_t* VT, const bf16_t* P, bf16_t* Z0, int b, int h, int qrow0, int nkeys) {
;     ...
;     for (int qb = 0; qb < 2; ++qb) {
;         float lt = lsum[qb]; lt += __shfl_xor(lt, 16); lt += __shfl_xor(lt, 32);
;         const float inv = 1.f / lt; const size_t row = (size_t)(qrow0 + wave * 32 + qb * 16 + fr);
; #pragma unroll
;         for (int db = 0; db < 4; ++db) { const int c4 = h * 64 + db * 16 + fq * 4; const u32x2 g = ld4(P + row * INP + OFF_GATE + c4);
;             const f32x4 v = o[qb][db] * inv; u32x2 w; w.x = cvt_pk_bf16(v[0] * siluf(bflo(g.x)), v[1] * siluf(bfhi(g.x))); w.y = cvt_pk_bf16(v[2] * siluf(bflo(g.y)), v[3] * siluf(bfhi(g.y)));
;             *(u32x2*)(Z0 + row * 256 + c4) = w; }
.LBB0_1008:
	s_waitcnt vmcnt(0)
	v_and_b32_e32 v2, 64, v199
	v_xor_b32_e32 v0, 16, v199
	v_add_u32_e32 v2, 64, v2
	v_cmp_lt_i32_e32 vcc, v0, v2
	s_lshl_b32 s1, s1, 7
	s_waitcnt lgkmcnt(0)
	v_lshlrev_b64 v[8:9], 9, v[90:91]
	v_cndmask_b32_e32 v0, v199, v0, vcc
	v_lshlrev_b32_e32 v3, 2, v0
	v_xor_b32_e32 v0, 32, v199
	v_cmp_lt_i32_e32 vcc, v0, v2
	v_lshl_add_u64 v[8:9], s[44:45], 0, v[8:9]
	s_nop 0
	v_cndmask_b32_e32 v0, v199, v0, vcc
	v_lshlrev_b32_e32 v34, 2, v0
	ds_bpermute_b32 v0, v3, v88
	s_waitcnt lgkmcnt(0)
	v_add_f32_e32 v0, v88, v0
	ds_bpermute_b32 v2, v34, v0
	s_waitcnt lgkmcnt(0)
	v_add_f32_e32 v0, v0, v2
	v_div_scale_f32 v2, s[4:5], v0, v0, 1.0
	v_rcp_f32_e32 v4, v2
	s_nop 0
	v_fma_f32 v5, -v2, v4, 1.0
	v_fmac_f32_e32 v4, v5, v4
	v_div_scale_f32 v5, vcc, 1.0, v0, 1.0
	v_mul_f32_e32 v6, v5, v4
	v_fma_f32 v7, -v2, v6, v5
	v_fmac_f32_e32 v6, v7, v4
	v_fma_f32 v2, -v2, v6, v5
	v_div_fmas_f32 v2, v2, v4, v6
	v_mov_b64_e32 v[4:5], s[42:43]
	v_div_fixup_f32 v2, v2, v0, 1.0
	v_mad_i64_i32 v[6:7], s[4:5], v90, s84, v[4:5]
	v_lshl_or_b32 v0, v170, 3, s1
	v_lshl_add_u64 v[6:7], v[6:7], 0, v[0:1]
	global_load_dwordx2 v[36:37], v[6:7], off offset:2368
	v_pk_mul_f32 v[40:41], v[82:83], v[2:3] op_sel_hi:[1,0]
	v_pk_mul_f32 v[38:39], v[84:85], v[2:3] op_sel_hi:[1,0]
	v_lshl_add_u64 v[8:9], v[8:9], 0, v[0:1]
	v_pk_mul_f32 v[32:33], v[32:33], v[2:3] op_sel_hi:[1,0]
	v_pk_mul_f32 v[30:31], v[30:31], v[2:3] op_sel_hi:[1,0]
	v_mad_i64_i32 v[4:5], s[4:5], v86, s84, v[4:5]
	v_lshl_add_u64 v[4:5], v[4:5], 0, v[0:1]
	s_waitcnt vmcnt(0) lgkmcnt(0)
	v_lshlrev_b32_e32 v35, 16, v36
	v_mul_f32_e32 v42, 0xbfb8aa3b, v35
	v_exp_f32_e32 v42, v42
	v_and_b32_e32 v36, 0xffff0000, v36
	v_add_f32_e32 v42, 1.0, v42
	v_rcp_f32_e32 v42, v42
	s_nop 0
	v_mul_f32_e32 v35, v42, v35
	v_mul_f32_e32 v35, v40, v35
	v_mul_f32_e32 v40, 0xbfb8aa3b, v36
	v_exp_f32_e32 v40, v40
	s_nop 0
	v_add_f32_e32 v40, 1.0, v40
	v_rcp_f32_e32 v40, v40
	s_nop 0
	v_mul_f32_e32 v36, v40, v36
	v_mul_f32_e32 v36, v41, v36
	v_cvt_pk_bf16_f32 v36, v35, v36
	v_lshlrev_b32_e32 v35, 16, v37
	v_mul_f32_e32 v40, 0xbfb8aa3b, v35
	v_exp_f32_e32 v40, v40
	v_and_b32_e32 v37, 0xffff0000, v37
	v_add_f32_e32 v40, 1.0, v40
	v_rcp_f32_e32 v40, v40
	s_nop 0
	v_mul_f32_e32 v35, v40, v35
	v_mul_f32_e32 v35, v38, v35
	v_mul_f32_e32 v38, 0xbfb8aa3b, v37
	v_exp_f32_e32 v38, v38
	v_pk_mul_f32 v[40:41], v[74:75], v[2:3] op_sel_hi:[1,0]
	v_add_f32_e32 v38, 1.0, v38
	v_rcp_f32_e32 v38, v38
	s_nop 0
	v_mul_f32_e32 v37, v38, v37
	v_mul_f32_e32 v37, v39, v37
	v_cvt_pk_bf16_f32 v37, v35, v37
	global_store_dwordx2 v[8:9], v[36:37], off
	global_load_dwordx2 v[36:37], v[6:7], off offset:2400
	v_pk_mul_f32 v[38:39], v[76:77], v[2:3] op_sel_hi:[1,0]
	s_waitcnt vmcnt(0) lgkmcnt(0)
	v_lshlrev_b32_e32 v35, 16, v36
	v_mul_f32_e32 v42, 0xbfb8aa3b, v35
	v_exp_f32_e32 v42, v42
	v_and_b32_e32 v36, 0xffff0000, v36
	v_add_f32_e32 v42, 1.0, v42
	v_rcp_f32_e32 v42, v42
	s_nop 0
	v_mul_f32_e32 v35, v42, v35
	v_mul_f32_e32 v35, v40, v35
	v_mul_f32_e32 v40, 0xbfb8aa3b, v36
	v_exp_f32_e32 v40, v40
	s_nop 0
	v_add_f32_e32 v40, 1.0, v40
	v_rcp_f32_e32 v40, v40
	s_nop 0
	v_mul_f32_e32 v36, v40, v36
	v_mul_f32_e32 v36, v41, v36
	v_cvt_pk_bf16_f32 v36, v35, v36
	v_lshlrev_b32_e32 v35, 16, v37
	v_mul_f32_e32 v40, 0xbfb8aa3b, v35
	v_exp_f32_e32 v40, v40
	v_and_b32_e32 v37, 0xffff0000, v37
	v_add_f32_e32 v40, 1.0, v40
	v_rcp_f32_e32 v40, v40
	s_nop 0
	v_mul_f32_e32 v35, v40, v35
	v_mul_f32_e32 v35, v38, v35
	v_mul_f32_e32 v38, 0xbfb8aa3b, v37
	v_exp_f32_e32 v38, v38
	v_pk_mul_f32 v[40:41], v[58:59], v[2:3] op_sel_hi:[1,0]
	v_add_f32_e32 v38, 1.0, v38
	v_rcp_f32_e32 v38, v38
	s_nop 0
	v_mul_f32_e32 v37, v38, v37
	v_mul_f32_e32 v37, v39, v37
	v_cvt_pk_bf16_f32 v37, v35, v37
	global_store_dwordx2 v[8:9], v[36:37], off offset:32
	global_load_dwordx2 v[36:37], v[6:7], off offset:2432
	v_pk_mul_f32 v[38:39], v[60:61], v[2:3] op_sel_hi:[1,0]
	s_waitcnt vmcnt(0) lgkmcnt(0)
	v_lshlrev_b32_e32 v35, 16, v36
	v_mul_f32_e32 v42, 0xbfb8aa3b, v35
	v_exp_f32_e32 v42, v42
	v_and_b32_e32 v36, 0xffff0000, v36
	v_add_f32_e32 v42, 1.0, v42
	v_rcp_f32_e32 v42, v42
	s_nop 0
	v_mul_f32_e32 v35, v42, v35
	v_mul_f32_e32 v35, v40, v35
	v_mul_f32_e32 v40, 0xbfb8aa3b, v36
	v_exp_f32_e32 v40, v40
	s_nop 0
	v_add_f32_e32 v40, 1.0, v40
	v_rcp_f32_e32 v40, v40
	s_nop 0
	v_mul_f32_e32 v36, v40, v36
	v_mul_f32_e32 v36, v41, v36
	v_cvt_pk_bf16_f32 v36, v35, v36
	v_lshlrev_b32_e32 v35, 16, v37
	v_mul_f32_e32 v40, 0xbfb8aa3b, v35
	v_exp_f32_e32 v40, v40
	v_and_b32_e32 v37, 0xffff0000, v37
	v_add_f32_e32 v40, 1.0, v40
	v_rcp_f32_e32 v40, v40
	s_nop 0
	v_mul_f32_e32 v35, v40, v35
	v_mul_f32_e32 v35, v38, v35
	v_mul_f32_e32 v38, 0xbfb8aa3b, v37
	v_exp_f32_e32 v38, v38
	s_nop 0
	v_add_f32_e32 v38, 1.0, v38
	v_rcp_f32_e32 v38, v38
	s_nop 0
	v_mul_f32_e32 v37, v38, v37
	v_mul_f32_e32 v37, v39, v37
	v_cvt_pk_bf16_f32 v37, v35, v37
	global_load_dwordx2 v[6:7], v[6:7], off offset:2464
	s_waitcnt vmcnt(0) lgkmcnt(0)
	v_lshlrev_b32_e32 v2, 16, v6
	v_mul_f32_e32 v35, 0xbfb8aa3b, v2
	v_exp_f32_e32 v35, v35
	v_and_b32_e32 v6, 0xffff0000, v6
	global_store_dwordx2 v[8:9], v[36:37], off offset:64
	v_add_f32_e32 v35, 1.0, v35
	v_rcp_f32_e32 v35, v35
	s_nop 0
	v_mul_f32_e32 v2, v35, v2
	v_mul_f32_e32 v2, v30, v2
	v_mul_f32_e32 v30, 0xbfb8aa3b, v6
	v_exp_f32_e32 v30, v30
	s_nop 0
	v_add_f32_e32 v30, 1.0, v30
	v_rcp_f32_e32 v30, v30
	s_nop 0
	v_mul_f32_e32 v6, v30, v6
	v_mul_f32_e32 v6, v31, v6
	v_cvt_pk_bf16_f32 v6, v2, v6
	v_lshlrev_b32_e32 v2, 16, v7
	v_mul_f32_e32 v30, 0xbfb8aa3b, v2
	v_exp_f32_e32 v30, v30
	v_and_b32_e32 v7, 0xffff0000, v7
	v_add_f32_e32 v30, 1.0, v30
	v_rcp_f32_e32 v30, v30
	s_nop 0
	v_mul_f32_e32 v2, v30, v2
	v_mul_f32_e32 v30, 0xbfb8aa3b, v7
	v_exp_f32_e32 v30, v30
	v_mul_f32_e32 v2, v32, v2
	v_add_f32_e32 v30, 1.0, v30
	v_rcp_f32_e32 v30, v30
	s_nop 0
	v_mul_f32_e32 v7, v30, v7
	v_mul_f32_e32 v7, v33, v7
	v_cvt_pk_bf16_f32 v7, v2, v7
	ds_bpermute_b32 v2, v3, v89
	global_store_dwordx2 v[8:9], v[6:7], off offset:96
	s_waitcnt lgkmcnt(0)
; __device__ __forceinline__ unsigned cvt_pk_bf16(float lo, float hi) { unsigned r; asm volatile("v_cvt_pk_bf16_f32 %0, %1, %2" : "=v"(r) : "v"(lo), "v"(hi)); return r; }
; __device__ __forceinline__ float bflo(unsigned w) { return __uint_as_float(w << 16); }
; __device__ __forceinline__ float bfhi(unsigned w) { return __uint_as_float(w & 0xffff0000u); }
; __device__ __forceinline__ float siluf(float x) { return x * __builtin_amdgcn_rcpf(1.f + __expf(-x)); }
; __device__ __forceinline__ void attn_unit(LAS unsigned char* lds, const bf16_t* QB, const bf16_t* KB, const bf16_t* VT, const bf16_t* P, bf16_t* Z0, int b, int h, int qrow0, int nkeys) {
;     ...
;     for (int qb = 0; qb < 2; ++qb) {
;         float lt = lsum[qb]; lt += __shfl_xor(lt, 16); lt += __shfl_xor(lt, 32);
;         const float inv = 1.f / lt; const size_t row = (size_t)(qrow0 + wave * 32 + qb * 16 + fr);
; #pragma unroll
;         for (int db = 0; db < 4; ++db) { const int c4 = h * 64 + db * 16 + fq * 4; const u32x2 g = ld4(P + row * INP + OFF_GATE + c4);
;             const f32x4 v = o[qb][db] * inv; u32x2 w; w.x = cvt_pk_bf16(v[0] * siluf(bflo(g.x)), v[1] * siluf(bfhi(g.x))); w.y = cvt_pk_bf16(v[2] * siluf(bflo(g.y)), v[3] * siluf(bfhi(g.y)));
;             *(u32x2*)(Z0 + row * 256 + c4) = w; }
	v_add_f32_e32 v2, v89, v2
	ds_bpermute_b32 v3, v34, v2
	s_waitcnt lgkmcnt(0)
	v_add_f32_e32 v2, v2, v3
	v_div_scale_f32 v3, s[4:5], v2, v2, 1.0
	v_rcp_f32_e32 v6, v3
	s_nop 0
	v_fma_f32 v7, -v3, v6, 1.0
	v_fmac_f32_e32 v6, v7, v6
	v_div_scale_f32 v7, vcc, 1.0, v2, 1.0
	v_mul_f32_e32 v8, v7, v6
	v_fma_f32 v9, -v3, v8, v7
	v_fmac_f32_e32 v8, v9, v6
	v_fma_f32 v3, -v3, v8, v7
	v_div_fmas_f32 v3, v3, v6, v8
	global_load_dwordx2 v[8:9], v[4:5], off offset:2368
	v_div_fixup_f32 v2, v3, v2, 1.0
	v_pk_mul_f32 v[28:29], v[28:29], v[2:3] op_sel_hi:[1,0]
	v_pk_mul_f32 v[26:27], v[26:27], v[2:3] op_sel_hi:[1,0]
	v_lshlrev_b64 v[6:7], 9, v[86:87]
	v_lshl_add_u64 v[6:7], s[44:45], 0, v[6:7]
	v_lshl_add_u64 v[6:7], v[6:7], 0, v[0:1]
	s_waitcnt vmcnt(0) lgkmcnt(0)
	v_lshlrev_b32_e32 v3, 16, v8
	v_mul_f32_e32 v30, 0xbfb8aa3b, v3
	v_exp_f32_e32 v30, v30
	v_and_b32_e32 v8, 0xffff0000, v8
	v_add_f32_e32 v30, 1.0, v30
	v_rcp_f32_e32 v30, v30
	s_nop 0
	v_mul_f32_e32 v3, v30, v3
	v_mul_f32_e32 v3, v26, v3
	v_mul_f32_e32 v26, 0xbfb8aa3b, v8
	v_exp_f32_e32 v26, v26
	s_nop 0
	v_add_f32_e32 v26, 1.0, v26
	v_rcp_f32_e32 v26, v26
	s_nop 0
	v_mul_f32_e32 v8, v26, v8
	v_mul_f32_e32 v8, v27, v8
	v_cvt_pk_bf16_f32 v8, v3, v8
	v_lshlrev_b32_e32 v3, 16, v9
	v_mul_f32_e32 v26, 0xbfb8aa3b, v3
	v_exp_f32_e32 v26, v26
	v_and_b32_e32 v9, 0xffff0000, v9
	v_add_f32_e32 v26, 1.0, v26
	v_rcp_f32_e32 v26, v26
	s_nop 0
	v_mul_f32_e32 v3, v26, v3
	v_mul_f32_e32 v26, 0xbfb8aa3b, v9
	v_exp_f32_e32 v26, v26
	v_mul_f32_e32 v3, v28, v3
	v_pk_mul_f32 v[24:25], v[24:25], v[2:3] op_sel_hi:[1,0]
	v_pk_mul_f32 v[22:23], v[22:23], v[2:3] op_sel_hi:[1,0]
	v_add_f32_e32 v26, 1.0, v26
	v_rcp_f32_e32 v26, v26
	s_nop 0
	v_mul_f32_e32 v9, v26, v9
	v_mul_f32_e32 v9, v29, v9
	v_cvt_pk_bf16_f32 v9, v3, v9
	global_store_dwordx2 v[6:7], v[8:9], off
	global_load_dwordx2 v[8:9], v[4:5], off offset:2400
	s_waitcnt vmcnt(0) lgkmcnt(0)
	v_lshlrev_b32_e32 v0, 16, v8
	v_mul_f32_e32 v3, 0xbfb8aa3b, v0
	v_exp_f32_e32 v3, v3
	s_nop 0
	v_add_f32_e32 v3, 1.0, v3
	v_rcp_f32_e32 v3, v3
	s_nop 0
	v_mul_f32_e32 v0, v3, v0
	v_and_b32_e32 v3, 0xffff0000, v8
	v_mul_f32_e32 v8, 0xbfb8aa3b, v3
	v_exp_f32_e32 v8, v8
	v_mul_f32_e32 v0, v22, v0
	v_add_f32_e32 v8, 1.0, v8
	v_rcp_f32_e32 v8, v8
	s_nop 0
	v_mul_f32_e32 v3, v8, v3
	v_mul_f32_e32 v3, v23, v3
	v_cvt_pk_bf16_f32 v8, v0, v3
	v_lshlrev_b32_e32 v0, 16, v9
	v_mul_f32_e32 v3, 0xbfb8aa3b, v0
	v_exp_f32_e32 v3, v3
	s_nop 0
	v_add_f32_e32 v3, 1.0, v3
	v_rcp_f32_e32 v3, v3
	s_nop 0
	v_mul_f32_e32 v0, v3, v0
	v_and_b32_e32 v3, 0xffff0000, v9
	v_mul_f32_e32 v9, 0xbfb8aa3b, v3
	v_exp_f32_e32 v9, v9
	v_mul_f32_e32 v0, v24, v0
	v_add_f32_e32 v9, 1.0, v9
	v_rcp_f32_e32 v9, v9
	s_nop 0
	v_mul_f32_e32 v3, v9, v3
	v_mul_f32_e32 v3, v25, v3
	v_cvt_pk_bf16_f32 v9, v0, v3
	global_store_dwordx2 v[6:7], v[8:9], off offset:32
	global_load_dwordx2 v[8:9], v[4:5], off offset:2432
	v_pk_mul_f32 v[20:21], v[20:21], v[2:3] op_sel_hi:[1,0]
	v_pk_mul_f32 v[18:19], v[18:19], v[2:3] op_sel_hi:[1,0]
	s_waitcnt vmcnt(0) lgkmcnt(0)
	v_lshlrev_b32_e32 v0, 16, v8
	v_mul_f32_e32 v3, 0xbfb8aa3b, v0
	v_exp_f32_e32 v3, v3
	s_nop 0
	v_add_f32_e32 v3, 1.0, v3
	v_rcp_f32_e32 v3, v3
	s_nop 0
	v_mul_f32_e32 v0, v3, v0
	v_and_b32_e32 v3, 0xffff0000, v8
	v_mul_f32_e32 v8, 0xbfb8aa3b, v3
	v_exp_f32_e32 v8, v8
	v_mul_f32_e32 v0, v18, v0
	v_add_f32_e32 v8, 1.0, v8
	v_rcp_f32_e32 v8, v8
	s_nop 0
	v_mul_f32_e32 v3, v8, v3
	v_mul_f32_e32 v3, v19, v3
	v_cvt_pk_bf16_f32 v8, v0, v3
	v_lshlrev_b32_e32 v0, 16, v9
	v_mul_f32_e32 v3, 0xbfb8aa3b, v0
	v_exp_f32_e32 v3, v3
	s_nop 0
	v_add_f32_e32 v3, 1.0, v3
	v_rcp_f32_e32 v3, v3
	s_nop 0
	v_mul_f32_e32 v0, v3, v0
	v_and_b32_e32 v3, 0xffff0000, v9
	v_mul_f32_e32 v9, 0xbfb8aa3b, v3
	v_exp_f32_e32 v9, v9
	v_mul_f32_e32 v0, v20, v0
	v_add_f32_e32 v9, 1.0, v9
	v_rcp_f32_e32 v9, v9
	s_nop 0
	v_mul_f32_e32 v3, v9, v3
	v_mul_f32_e32 v3, v21, v3
	v_cvt_pk_bf16_f32 v9, v0, v3
	global_load_dwordx2 v[4:5], v[4:5], off offset:2464
	s_waitcnt vmcnt(0) lgkmcnt(0)
	v_lshlrev_b32_e32 v0, 16, v4
	global_store_dwordx2 v[6:7], v[8:9], off offset:64
	v_pk_mul_f32 v[8:9], v[16:17], v[2:3] op_sel_hi:[1,0]
	v_pk_mul_f32 v[2:3], v[14:15], v[2:3] op_sel_hi:[1,0]
	v_mul_f32_e32 v14, 0xbfb8aa3b, v0
	v_exp_f32_e32 v14, v14
	s_nop 0
	v_add_f32_e32 v14, 1.0, v14
	v_rcp_f32_e32 v14, v14
	s_nop 0
	v_mul_f32_e32 v0, v14, v0
	v_mul_f32_e32 v0, v2, v0
	v_and_b32_e32 v2, 0xffff0000, v4
	v_mul_f32_e32 v4, 0xbfb8aa3b, v2
	v_exp_f32_e32 v4, v4
	s_nop 0
	v_add_f32_e32 v4, 1.0, v4
	v_rcp_f32_e32 v4, v4
	s_nop 0
	v_mul_f32_e32 v2, v4, v2
	v_mul_f32_e32 v2, v3, v2
	v_cvt_pk_bf16_f32 v2, v0, v2
	v_lshlrev_b32_e32 v0, 16, v5
	v_mul_f32_e32 v3, 0xbfb8aa3b, v0
	v_exp_f32_e32 v3, v3
	s_nop 0
	v_add_f32_e32 v3, 1.0, v3
	v_rcp_f32_e32 v3, v3
	s_nop 0
	v_mul_f32_e32 v0, v3, v0
	v_and_b32_e32 v3, 0xffff0000, v5
	v_mul_f32_e32 v4, 0xbfb8aa3b, v3
	v_exp_f32_e32 v4, v4
	v_mul_f32_e32 v0, v8, v0
	v_add_f32_e32 v4, 1.0, v4
	v_rcp_f32_e32 v4, v4
	s_nop 0
	v_mul_f32_e32 v3, v4, v3
	v_mul_f32_e32 v3, v9, v3
	v_cvt_pk_bf16_f32 v3, v0, v3
	global_store_dwordx2 v[6:7], v[2:3], off offset:96

; #define LAS __attribute__((address_space(3)))
; __device__ __forceinline__ int opaque_tid() { int t; asm volatile("v_mov_b32 %0, %1" : "=v"(t) : "v"((int)threadIdx.x)); return t; }
; #define ATT_LOAD(S_, tt) do { const bf16_t* kt_ = kg + (size_t)(tt) * 64 * 96; rk0[S_] = ld8(kt_ + kp0 * 8); if (kp1 < 768) rk1[S_] = ld8(kt_ + kp1 * 8); rv[S_] = ld8(vg + (size_t)vd * NKEY + (tt) * 64 + vpart * 8); } while (0)
; #define ATT_STORE(S_, bufi) do { LAS unsigned char* kb_ = lds + (bufi) * KBUF; *(LAS u32x4*)(kb_ + (kp0 / 12) * KST + (kp0 % 12) * 16) = rk0[S_]; if (kp1 < 768) *(LAS u32x4*)(kb_ + (kp1 / 12) * KST + (kp1 % 12) * 16) = rk1[S_]; \
;         *(LAS u32x4*)(lds + VOFF + (bufi) * VBUF + vd * VST + vpart * 16) = rv[S_]; } while (0)
; __device__ __forceinline__ void attn_unit(LAS unsigned char* lds, const bf16_t* QB, const bf16_t* KB, const bf16_t* VT, const bf16_t* P, bf16_t* Z0, int b, int h, int qrow0, int nkeys) {
;     const int tid = opaque_tid(), lane = tid & 63, wave = tid >> 6, fr = lane & 15, fq = lane >> 4;
;     constexpr int KST = 208, VST = 144, KBUF = 64 * KST, VBUF = 64 * VST, VOFF = 2 * KBUF;
;     bf16x8 qf[2][3];
; #pragma unroll
;     for (int qb = 0; qb < 2; ++qb)
; #pragma unroll
;         for (int ks = 0; ks < 3; ++ks) qf[qb][ks] = asfrag(ld8(QB + (size_t)(qrow0 + wave * 32 + qb * 16 + fr) * 384 + h * 96 + ks * 32 + fq * 8));
;     const bf16_t* kg = KB + (size_t)(b * 4 + h) * NKEY * 96;
;     const bf16_t* vg = VT + (size_t)(b * 4 + h) * 64 * NKEY;
;     const int kp0 = tid, kp1 = tid + 512;
;     const int vd = tid >> 3, vpart = tid & 7;
;     u32x4 rk0[2], rk1[2], rv[2];
;     const int ntile = nkeys >> 6;
;     ...
;     __syncthreads();
;     ATT_LOAD(0, 0); ATT_STORE(0, 0);
;     __syncthreads();
;     if (1 < ntile) ATT_LOAD(0, 1);
;     if (2 < ntile) ATT_LOAD(1, 2);
; __global__ void __launch_bounds__(512, 2) fwd_kernel(KArgs a) {
;     ...
;                 else { const int h = (u - 256) & 3, b = (u - 256) >> 2; attn_unit(lds, QB, KB, VT, P, Z0, b, h, ML + b * 256, CTXL); }
.LBB0_1010:
	s_cmpk_gt_i32 s46, 0xff
	s_mov_b64 s[4:5], -1
	s_cbranch_scc0 .LBB0_1036
	s_add_i32 s6, s46, 0xffffff00
	s_lshl_b32 s4, s6, 6
	s_and_b32 s4, s4, 0x7fffff00
	s_and_b32 s1, s46, 3
	s_addk_i32 s4, 0x4000
	v_mov_b32 v21, v194
	s_movk_i32 s7, 0xff
	v_and_b32_e32 v22, 15, v21
	v_ashrrev_i32_e32 v0, 1, v21
	v_or_b32_e32 v2, s4, v22
	s_mul_i32 s4, s1, 0xc0
	v_bfe_u32 v168, v21, 4, 2
	v_and_b32_e32 v0, 0xffffffe0, v0
	s_add_u32 s4, s28, s4
	v_add_u32_e32 v90, v2, v0
	s_addc_u32 s5, s29, 0
	v_lshlrev_b32_e32 v0, 4, v168
	v_lshl_add_u64 v[2:3], s[4:5], 0, v[0:1]
	v_or_b32_e32 v86, 16, v90
	v_mad_i64_i32 v[4:5], s[4:5], v90, s50, v[2:3]
	v_mad_i64_i32 v[2:3], s[4:5], v86, s50, v[2:3]
	s_mul_i32 s4, s6, 0x6c000
	s_mul_hi_u32 s5, s6, 0x6c000
	s_add_u32 s4, s30, s4
	v_lshlrev_b32_e32 v18, 3, v21
	global_load_dwordx4 v[30:33], v[4:5], off
	global_load_dwordx4 v[34:37], v[4:5], off offset:64
	global_load_dwordx4 v[38:41], v[4:5], off offset:128
	global_load_dwordx4 v[42:45], v[2:3], off
	global_load_dwordx4 v[46:49], v[2:3], off offset:64
	global_load_dwordx4 v[50:53], v[2:3], off offset:128
	s_addc_u32 s5, s31, s5
	v_ashrrev_i32_e32 v19, 31, v18
	v_lshl_add_u64 v[2:3], v[18:19], 1, s[4:5]
	s_waitcnt lgkmcnt(0)
	s_barrier
	global_load_dwordx4 v[6:9], v[2:3], off
	v_add_u32_e32 v23, 0x200, v21
	v_mov_b32_e32 v2, 0
	v_cmp_lt_i32_e32 vcc, s7, v21
	v_cmp_gt_i32_e64 s[36:37], s14, v21
	v_lshlrev_b32_e32 v20, 3, v23
	v_mov_b32_e32 v3, 0
	v_mov_b32_e32 v4, 0
	v_mov_b32_e32 v5, 0
	v_mov_b32_e32 v54, 0
	v_mov_b32_e32 v55, v2
	v_mov_b32_e32 v56, v2
	v_mov_b32_e32 v57, v2
	s_and_saveexec_b64 s[20:21], s[36:37]
	s_cbranch_execz .LBB0_1013
	v_lshlrev_b32_e32 v2, 3, v23
	v_ashrrev_i32_e32 v3, 31, v2
	v_lshl_add_u64 v[2:3], v[2:3], 1, s[4:5]
	global_load_dwordx4 v[2:5], v[2:3], off
	s_waitcnt vmcnt(0) lgkmcnt(0)
	v_mov_b32_e32 v54, v2
	v_mov_b32_e32 v55, v3
	v_mov_b32_e32 v56, v4
	v_mov_b32_e32 v57, v5
.LBB0_1013:
	s_or_b64 exec, exec, s[20:21]
	s_mul_hi_u32 s7, s6, 0x48000
	s_mul_i32 s6, s6, 0x48000
	s_add_u32 s6, s34, s6
	s_addc_u32 s7, s35, s7
	v_ashrrev_i32_e32 v24, 3, v21
	v_and_b32_e32 v0, 7, v21
	v_mov_b64_e32 v[14:15], s[6:7]
	v_mad_i64_i32 v[14:15], s[6:7], v24, s88, v[14:15]
	v_lshlrev_b32_e32 v0, 4, v0
	v_lshl_add_u64 v[92:93], v[14:15], 0, v[0:1]
	global_load_dwordx4 v[14:17], v[92:93], off
	s_mov_b32 s6, 0x2aaaaaab
	v_mul_hi_i32 v25, v21, s6
	v_lshrrev_b32_e32 v26, 31, v25
	v_ashrrev_i32_e32 v25, 1, v25
	v_add_u32_e32 v25, v25, v26
	v_mul_lo_u32 v26, v25, s33
	v_mul_lo_u32 v25, v25, 12
	v_sub_u32_e32 v21, v21, v25
	v_add_u32_e32 v26, 0, v26
	v_lshlrev_b32_e32 v21, 4, v21
	v_add_u32_e32 v169, v26, v21
	s_waitcnt vmcnt(0) lgkmcnt(0)
	ds_write_b128 v169, v[6:9]
	v_mul_hi_i32 v7, v23, s6
	v_lshrrev_b32_e32 v6, 31, v7
	v_ashrrev_i32_e32 v7, 1, v7
	s_and_saveexec_b64 s[20:21], s[36:37]
	s_cbranch_execz .LBB0_1015
	v_add_u32_e32 v8, v7, v6
	v_mul_lo_u32 v9, v8, s33
	v_mul_lo_u32 v8, v8, 12
	v_sub_u32_e32 v8, v23, v8
	v_lshlrev_b32_e32 v8, 4, v8
	v_add3_u32 v8, 0, v9, v8
	ds_write_b128 v8, v[2:5]
.LBB0_1015:
	s_or_b64 exec, exec, s[20:21]
	v_mul_lo_u32 v2, v24, s15
	s_add_u32 s20, s4, 0x3000
	v_add_u32_e32 v2, 0, v2
	s_addc_u32 s21, s5, 0
	v_add_u32_e32 v170, v2, v0
	v_lshl_add_u64 v[2:3], v[18:19], 1, s[20:21]
	ds_write_b128 v170, v[14:17] offset:26624
	s_waitcnt lgkmcnt(0)
	s_barrier
	global_load_dwordx4 v[58:61], v[2:3], off
	s_and_saveexec_b64 s[6:7], vcc
	s_xor_b64 s[22:23], exec, s[6:7]
	v_lshlrev_b32_e32 v0, 3, v23
	s_andn2_saveexec_b64 s[22:23], s[22:23]
	s_cbranch_execz .LBB0_1019
	v_ashrrev_i32_e32 v21, 31, v20
	v_lshl_add_u64 v[2:3], v[20:21], 1, s[20:21]
	global_load_dwordx4 v[54:57], v[2:3], off
	v_mov_b32_e32 v0, v20
.LBB0_1019:
	s_or_b64 exec, exec, s[22:23]
	s_add_u32 s20, s4, 0x6000
	s_addc_u32 s21, s5, 0
	v_lshl_add_u64 v[2:3], v[18:19], 1, s[20:21]
	global_load_dwordx4 v[74:77], v[92:93], off offset:128
	global_load_dwordx4 v[62:65], v[2:3], off
	s_and_saveexec_b64 s[6:7], vcc
	s_xor_b64 s[22:23], exec, s[6:7]
	v_mov_b64_e32 v[4:5], v[0:1]
	s_or_saveexec_b64 s[22:23], s[22:23]
	v_mov_b32_e32 v2, 0
	v_mov_b32_e32 v70, 0
	v_mov_b32_e32 v71, 0
	v_mov_b32_e32 v72, 0
	v_mov_b32_e32 v73, 0
	s_xor_b64 exec, exec, s[22:23]
	s_cbranch_execz .LBB0_1023
	v_ashrrev_i32_e32 v5, 31, v0
	v_mov_b32_e32 v4, v0
	v_lshl_add_u64 v[8:9], v[4:5], 1, s[20:21]
	global_load_dwordx4 v[70:73], v[8:9], off
.LBB0_1023:
	s_or_b64 exec, exec, s[22:23]
	global_load_dwordx4 v[78:81], v[92:93], off offset:256
	v_lshlrev_b32_e32 v0, 3, v168
	v_lshl_add_u32 v3, v168, 4, 0
	v_sub_u32_e32 v8, v3, v0
	v_add_u32_e32 v0, v7, v6
	v_mul_lo_u32 v6, v0, s33
	v_mul_lo_u32 v0, v0, 12
	s_add_u32 s4, s4, 0x9000
	v_sub_u32_e32 v0, v23, v0
	v_mul_u32_u24_e32 v7, 0xd0, v22
	v_mul_u32_u24_e32 v9, 0x90, v22
	s_addc_u32 s5, s5, 0
	v_ashrrev_i32_e32 v91, 31, v90
	v_ashrrev_i32_e32 v87, 31, v86
	v_lshlrev_b32_e32 v0, 4, v0
	v_add_u32_e32 v171, 0, v6
	v_lshl_add_u64 v[94:95], v[18:19], 1, s[4:5]
	v_lshl_add_u64 v[96:97], v[4:5], 1, s[4:5]
	s_mov_b64 s[4:5], -1
	v_add_u32_e32 v172, v3, v7
	v_add_u32_e32 v173, v8, v9
	v_mov_b32_e32 v3, v2
	v_mov_b32_e32 v4, v2
	v_mov_b32_e32 v5, v2
	v_mov_b32_e32 v6, v2
	v_mov_b32_e32 v7, v2
	v_mov_b32_e32 v8, v2
	v_mov_b32_e32 v9, v2
	v_mov_b32_e32 v14, v2
	v_mov_b32_e32 v15, v2
	v_mov_b32_e32 v16, v2
	v_mov_b32_e32 v17, v2
	v_mov_b32_e32 v18, v2
	v_mov_b32_e32 v19, v2
	v_mov_b32_e32 v20, v2
	v_mov_b32_e32 v21, v2
	v_mov_b32_e32 v22, v2
	v_mov_b32_e32 v23, v2
	v_mov_b32_e32 v24, v2
	v_mov_b32_e32 v25, v2
	v_mov_b32_e32 v26, v2
	v_mov_b32_e32 v27, v2
	v_mov_b32_e32 v28, v2
	v_mov_b32_e32 v29, v2
	v_mov_b32_e32 v66, v2
	v_mov_b32_e32 v67, v2
	v_mov_b32_e32 v68, v2
	v_mov_b32_e32 v69, v2
	v_mov_b32_e32 v82, v2
	v_mov_b32_e32 v83, v2
	v_mov_b32_e32 v84, v2
	v_mov_b32_e32 v85, v2
	v_mov_b32_e32 v88, v2
	v_mov_b32_e32 v89, v2
	s_branch .LBB0_1026

; #define LAS __attribute__((address_space(3)))
; __device__ __forceinline__ void attn_unit(LAS unsigned char* lds, const bf16_t* QB, const bf16_t* KB, const bf16_t* VT, const bf16_t* P, bf16_t* Z0, int b, int h, int qrow0, int nkeys) {
;     ...
;     for (int t2 = 0; t2 < ntile; t2 += 2) {
; #pragma unroll
;       for (int half = 0; half < 2; ++half) { const int tt = t2 + half; if (tt < ntile) {
;         const int cur = half;
;         const LAS unsigned char* kb = lds + cur * KBUF; const LAS unsigned char* vb = lds + VOFF + cur * VBUF;
;         f32x4 s[2][4];
; #pragma unroll
;         for (int kbk = 0; kbk < 4; ++kbk) { s[0][kbk] = (f32x4){0.f, 0.f, 0.f, 0.f}; s[1][kbk] = s[0][kbk];
; #pragma unroll
;             for (int ks = 0; ks < 3; ++ks) { const bf16x8 kf = *(const LAS bf16x8*)(kb + (kbk * 16 + fr) * KST + ks * 64 + fq * 16);
;                 s[0][kbk] = MFMA16(kf, qf[0][ks], s[0][kbk]); s[1][kbk] = MFMA16(kf, qf[1][ks], s[1][kbk]); } }
;         bf16x8 pf[2][2];
; #pragma unroll
;         for (int qb = 0; qb < 2; ++qb) {
;             float ps = 0.f;
; #pragma unroll
;             for (int kbk = 0; kbk < 4; ++kbk)
; #pragma unroll
;                 for (int q = 0; q < 4; ++q) { const float pv = __builtin_amdgcn_exp2f(s[qb][kbk][q]); s[qb][kbk][q] = pv; ps += pv; }
;             lsum[qb] += ps;
; #pragma unroll
;             for (int k2 = 0; k2 < 2; ++k2) { u32x4 w; w.x = cvt_pk_bf16(s[qb][2 * k2][0], s[qb][2 * k2][1]); w.y = cvt_pk_bf16(s[qb][2 * k2][2], s[qb][2 * k2][3]);
;                 w.z = cvt_pk_bf16(s[qb][2 * k2 + 1][0], s[qb][2 * k2 + 1][1]); w.w = cvt_pk_bf16(s[qb][2 * k2 + 1][2], s[qb][2 * k2 + 1][3]); pf[qb][k2] = asfrag(w); }
;         }
; #pragma unroll
;         for (int db = 0; db < 4; ++db)
; #pragma unroll
;             for (int k2 = 0; k2 < 2; ++k2) { const LAS unsigned char* vp = vb + (db * 16 + fr) * VST + (k2 * 32 + fq * 4) * 2;
;                 const u32x2 lo = *(const LAS u32x2*)vp, hi = *(const LAS u32x2*)(vp + 32);
;                 const bf16x8 vf = asfrag((u32x4){lo.x, lo.y, hi.x, hi.y});
;                 o[0][db] = MFMA16(vf, pf[0][k2], o[0][db]); o[1][db] = MFMA16(vf, pf[1][k2], o[1][db]); }
;         if (tt + 1 < ntile) ATT_STORE(half, cur ^ 1);
;         __syncthreads();
;         if (tt + 3 < ntile) ATT_LOAD(half, tt + 3);
;       } }
.LBB0_1026:
	ds_read_b128 v[98:101], v172
	ds_read_b128 v[102:105], v172 offset:64
	s_waitcnt lgkmcnt(0)
	v_mfma_f32_16x16x32_bf16 v[106:109], v[98:101], v[30:33], 0
	v_mfma_f32_16x16x32_bf16 v[98:101], v[98:101], v[42:45], 0
	v_mfma_f32_16x16x32_bf16 v[106:109], v[102:105], v[34:37], v[106:109]
	v_mfma_f32_16x16x32_bf16 v[98:101], v[102:105], v[46:49], v[98:101]
	ds_read_b128 v[102:105], v172 offset:128
	ds_read_b128 v[110:113], v172 offset:3328
	s_waitcnt lgkmcnt(0)
	v_mfma_f32_16x16x32_bf16 v[106:109], v[102:105], v[38:41], v[106:109]
	v_mfma_f32_16x16x32_bf16 v[130:133], v[102:105], v[50:53], v[98:101]
	s_nop 6
	v_exp_f32_e32 v126, v109
	v_mfma_f32_16x16x32_bf16 v[98:101], v[110:113], v[30:33], 0
	v_mfma_f32_16x16x32_bf16 v[102:105], v[110:113], v[42:45], 0
	ds_read_b128 v[110:113], v172 offset:3392
	ds_read_b128 v[114:117], v172 offset:3456
	v_exp_f32_e32 v127, v133
	s_waitcnt lgkmcnt(0)
	v_mfma_f32_16x16x32_bf16 v[102:105], v[110:113], v[46:49], v[102:105]
	v_mfma_f32_16x16x32_bf16 v[98:101], v[110:113], v[34:37], v[98:101]
	v_mfma_f32_16x16x32_bf16 v[134:137], v[114:117], v[50:53], v[102:105]
	s_nop 5
	ds_read_b128 v[102:105], v172 offset:6656
	ds_read_b128 v[110:113], v172 offset:6720
	v_exp_f32_e32 v125, v134
	v_mfma_f32_16x16x32_bf16 v[98:101], v[114:117], v[38:41], v[98:101]
	v_exp_f32_e32 v123, v135
	v_exp_f32_e32 v129, v136
	s_waitcnt lgkmcnt(0)
	v_mfma_f32_16x16x32_bf16 v[114:117], v[102:105], v[30:33], 0
	v_mfma_f32_16x16x32_bf16 v[102:105], v[102:105], v[42:45], 0
	s_nop 2
	v_exp_f32_e32 v124, v98
	v_exp_f32_e32 v122, v99
	v_exp_f32_e32 v128, v100
	v_mfma_f32_16x16x32_bf16 v[114:117], v[110:113], v[34:37], v[114:117]
	v_mfma_f32_16x16x32_bf16 v[102:105], v[110:113], v[46:49], v[102:105]
	ds_read_b128 v[110:113], v172 offset:6784
	ds_read_b128 v[118:121], v172 offset:9984
	s_waitcnt lgkmcnt(0)
	v_mfma_f32_16x16x32_bf16 v[138:141], v[110:113], v[38:41], v[114:117]
	s_nop 2
	v_exp_f32_e32 v116, v108
	v_mfma_f32_16x16x32_bf16 v[142:145], v[110:113], v[50:53], v[102:105]
	ds_read_b128 v[110:113], v172 offset:10048
	ds_read_b128 v[146:149], v172 offset:10112
	v_exp_f32_e32 v114, v101
	v_exp_f32_e32 v108, v140
	v_mfma_f32_16x16x32_bf16 v[102:105], v[118:121], v[30:33], 0
	v_exp_f32_e32 v117, v132
	v_exp_f32_e32 v115, v137
	s_nop 0
	v_exp_f32_e32 v109, v144
	v_mfma_f32_16x16x32_bf16 v[156:159], v[118:121], v[42:45], 0
	v_exp_f32_e32 v120, v106
	v_exp_f32_e32 v106, v141
	v_exp_f32_e32 v118, v107
	s_waitcnt lgkmcnt(0)
	v_mfma_f32_16x16x32_bf16 v[102:105], v[110:113], v[34:37], v[102:105]
	v_exp_f32_e32 v121, v130
	v_exp_f32_e32 v119, v131
	v_cvt_pk_bf16_f32 v130, v120, v118
	v_mfma_f32_16x16x32_bf16 v[156:159], v[110:113], v[46:49], v[156:159]
	v_exp_f32_e32 v112, v138
	v_exp_f32_e32 v110, v139
	v_cvt_pk_bf16_f32 v131, v116, v126
	v_mfma_f32_16x16x32_bf16 v[98:101], v[146:149], v[38:41], v[102:105]
	v_cvt_pk_bf16_f32 v132, v124, v122
	v_cvt_pk_bf16_f32 v133, v128, v114
	v_exp_f32_e32 v113, v142
	v_mfma_f32_16x16x32_bf16 v[138:141], v[146:149], v[50:53], v[156:159]
	v_exp_f32_e32 v111, v143
	s_nop 4
	v_exp_f32_e32 v104, v98
	v_exp_f32_e32 v102, v99
	v_add_u32_e32 v156, 0x6800, v173
	v_exp_f32_e32 v100, v100
	v_exp_f32_e32 v98, v101
	v_exp_f32_e32 v107, v145
	v_exp_f32_e32 v105, v138
	v_exp_f32_e32 v103, v139
	v_exp_f32_e32 v101, v140
	v_exp_f32_e32 v99, v141
	v_cvt_pk_bf16_f32 v134, v112, v110
	v_cvt_pk_bf16_f32 v135, v108, v106
	v_cvt_pk_bf16_f32 v136, v104, v102
	v_cvt_pk_bf16_f32 v137, v100, v98
	v_cvt_pk_bf16_f32 v138, v121, v119
	v_cvt_pk_bf16_f32 v139, v117, v127
	v_cvt_pk_bf16_f32 v140, v125, v123
	v_cvt_pk_bf16_f32 v141, v129, v115
	v_cvt_pk_bf16_f32 v142, v113, v111
	v_cvt_pk_bf16_f32 v143, v109, v107
	v_cvt_pk_bf16_f32 v144, v105, v103
	v_cvt_pk_bf16_f32 v145, v101, v99
	ds_read2_b64 v[146:149], v156 offset1:4
	ds_read2_b64 v[156:159], v156 offset0:8 offset1:12
	s_waitcnt lgkmcnt(0)
	v_mfma_f32_16x16x32_bf16 v[82:85], v[146:149], v[130:133], v[82:85]
	v_mfma_f32_16x16x32_bf16 v[146:149], v[146:149], v[138:141], v[18:21]
	v_mfma_f32_16x16x32_bf16 v[18:21], v[156:159], v[134:137], v[82:85]
	v_mfma_f32_16x16x32_bf16 v[82:85], v[156:159], v[142:145], v[146:149]
	v_add_u32_e32 v156, 0x7000, v173
	s_nop 4
	ds_read2_b64 v[146:149], v156 offset0:32 offset1:36
	ds_read2_b64 v[156:159], v156 offset0:40 offset1:44
	s_waitcnt lgkmcnt(0)
	v_mfma_f32_16x16x32_bf16 v[66:69], v[146:149], v[130:133], v[66:69]
	v_mfma_f32_16x16x32_bf16 v[146:149], v[146:149], v[138:141], v[14:17]
	v_mfma_f32_16x16x32_bf16 v[14:17], v[156:159], v[134:137], v[66:69]
	v_mfma_f32_16x16x32_bf16 v[66:69], v[156:159], v[142:145], v[146:149]
	v_add_u32_e32 v156, 0x7800, v173
	s_nop 4
	ds_read2_b64 v[146:149], v156 offset0:64 offset1:68
	ds_read2_b64 v[156:159], v156 offset0:72 offset1:76
	s_waitcnt lgkmcnt(0)
	v_mfma_f32_16x16x32_bf16 v[26:29], v[146:149], v[130:133], v[26:29]
	v_mfma_f32_16x16x32_bf16 v[146:149], v[146:149], v[138:141], v[6:9]
	v_mfma_f32_16x16x32_bf16 v[6:9], v[156:159], v[134:137], v[26:29]
	v_mfma_f32_16x16x32_bf16 v[26:29], v[156:159], v[142:145], v[146:149]
	v_add_u32_e32 v156, 0x8000, v173
	s_nop 4
	ds_read2_b64 v[146:149], v156 offset0:96 offset1:100
	s_waitcnt lgkmcnt(0)
	v_mfma_f32_16x16x32_bf16 v[22:25], v[146:149], v[130:133], v[22:25]
	v_mfma_f32_16x16x32_bf16 v[130:133], v[146:149], v[138:141], v[2:5]
	ds_read2_b64 v[138:141], v156 offset0:104 offset1:108
	s_waitcnt vmcnt(0)
	ds_write_b128 v169, v[58:61] offset:13312
	s_waitcnt lgkmcnt(1)
	v_mfma_f32_16x16x32_bf16 v[2:5], v[138:141], v[134:137], v[22:25]
	v_mfma_f32_16x16x32_bf16 v[22:25], v[138:141], v[142:145], v[130:133]
	s_and_saveexec_b64 s[20:21], s[36:37]
	s_nop 1
	v_add_u32_e32 v130, v171, v0
	ds_write_b128 v130, v[54:57] offset:13312
	s_or_b64 exec, exec, s[20:21]
	v_cndmask_b32_e64 v130, 0, 1, s[4:5]
	v_cmp_ne_u32_e64 s[38:39], 1, v130
	s_andn2_b64 vcc, exec, s[4:5]
	ds_write_b128 v170, v[74:77] offset:35840
	s_waitcnt lgkmcnt(0)
	s_barrier
	s_cbranch_vccnz .LBB0_1032
	global_load_dwordx4 v[58:61], v[94:95], off
	s_and_saveexec_b64 s[20:21], s[36:37]
	s_cbranch_execz .LBB0_1031
	global_load_dwordx4 v[54:57], v[96:97], off
.LBB0_1031:
	s_or_b64 exec, exec, s[20:21]
	global_load_dwordx4 v[74:77], v[92:93], off offset:384

; __device__ __forceinline__ unsigned cvt_pk_bf16(float lo, float hi) { unsigned r; asm volatile("v_cvt_pk_bf16_f32 %0, %1, %2" : "=v"(r) : "v"(lo), "v"(hi)); return r; }
; __device__ __forceinline__ float bflo(unsigned w) { return __uint_as_float(w << 16); }
; __device__ __forceinline__ float bfhi(unsigned w) { return __uint_as_float(w & 0xffff0000u); }
; __device__ __forceinline__ float siluf(float x) { return x * __builtin_amdgcn_rcpf(1.f + __expf(-x)); }
; __device__ __forceinline__ void attn_unit(LAS unsigned char* lds, const bf16_t* QB, const bf16_t* KB, const bf16_t* VT, const bf16_t* P, bf16_t* Z0, int b, int h, int qrow0, int nkeys) {
;     ...
; #pragma unroll
;     for (int qb = 0; qb < 2; ++qb) {
;         float lt = lsum[qb]; lt += __shfl_xor(lt, 16); lt += __shfl_xor(lt, 32);
;         const float inv = 1.f / lt; const size_t row = (size_t)(qrow0 + wave * 32 + qb * 16 + fr);
; #pragma unroll
;         for (int db = 0; db < 4; ++db) { const int c4 = h * 64 + db * 16 + fq * 4; const u32x2 g = ld4(P + row * INP + OFF_GATE + c4);
;             const f32x4 v = o[qb][db] * inv; u32x2 w; w.x = cvt_pk_bf16(v[0] * siluf(bflo(g.x)), v[1] * siluf(bfhi(g.x))); w.y = cvt_pk_bf16(v[2] * siluf(bflo(g.y)), v[3] * siluf(bfhi(g.y)));
;             *(u32x2*)(Z0 + row * 256 + c4) = w; }
;     }
.LBB0_1035:
	v_and_b32_e32 v30, 64, v199
	v_xor_b32_e32 v0, 16, v199
	v_add_u32_e32 v30, 64, v30
	v_cmp_lt_i32_e32 vcc, v0, v30
	s_lshl_b32 s1, s1, 7
	v_lshlrev_b64 v[36:37], 9, v[90:91]
	v_cndmask_b32_e32 v0, v199, v0, vcc
	v_lshlrev_b32_e32 v33, 2, v0
	v_xor_b32_e32 v0, 32, v199
	v_cmp_lt_i32_e32 vcc, v0, v30
	v_lshl_add_u64 v[36:37], s[44:45], 0, v[36:37]
	s_nop 0
	v_cndmask_b32_e32 v0, v199, v0, vcc
	v_lshlrev_b32_e32 v38, 2, v0
	ds_bpermute_b32 v0, v33, v88
	s_waitcnt lgkmcnt(0)
	v_add_f32_e32 v0, v88, v0
	ds_bpermute_b32 v30, v38, v0
	s_waitcnt lgkmcnt(0)
	v_add_f32_e32 v0, v0, v30
	v_div_scale_f32 v30, s[4:5], v0, v0, 1.0
	v_rcp_f32_e32 v31, v30
	s_nop 0
	v_fma_f32 v32, -v30, v31, 1.0
	v_fmac_f32_e32 v31, v32, v31
	v_div_scale_f32 v32, vcc, 1.0, v0, 1.0
	v_mul_f32_e32 v34, v32, v31
	v_fma_f32 v35, -v30, v34, v32
	v_fmac_f32_e32 v34, v35, v31
	v_fma_f32 v30, -v30, v34, v32
	v_div_fmas_f32 v30, v30, v31, v34
	v_div_fixup_f32 v32, v30, v0, 1.0
	v_mov_b64_e32 v[30:31], s[42:43]
	v_mad_i64_i32 v[34:35], s[4:5], v90, s84, v[30:31]
	v_lshl_or_b32 v0, v168, 3, s1
	v_lshl_add_u64 v[34:35], v[34:35], 0, v[0:1]
	global_load_dwordx2 v[40:41], v[34:35], off offset:2368
	v_pk_mul_f32 v[44:45], v[82:83], v[32:33] op_sel_hi:[1,0]
	v_pk_mul_f32 v[42:43], v[84:85], v[32:33] op_sel_hi:[1,0]
	v_lshl_add_u64 v[36:37], v[36:37], 0, v[0:1]
	v_pk_mul_f32 v[26:27], v[26:27], v[32:33] op_sel_hi:[1,0]
	v_pk_mul_f32 v[28:29], v[28:29], v[32:33] op_sel_hi:[1,0]
	v_pk_mul_f32 v[22:23], v[22:23], v[32:33] op_sel_hi:[1,0]
	v_pk_mul_f32 v[24:25], v[24:25], v[32:33] op_sel_hi:[1,0]
	s_waitcnt vmcnt(0) lgkmcnt(0)
	v_lshlrev_b32_e32 v39, 16, v40
	v_mul_f32_e32 v46, 0xbfb8aa3b, v39
	v_exp_f32_e32 v46, v46
	v_and_b32_e32 v40, 0xffff0000, v40
	v_add_f32_e32 v46, 1.0, v46
	v_rcp_f32_e32 v46, v46
	s_nop 0
	v_mul_f32_e32 v39, v46, v39
	v_mul_f32_e32 v39, v44, v39
	v_mul_f32_e32 v44, 0xbfb8aa3b, v40
	v_exp_f32_e32 v44, v44
	s_nop 0
	v_add_f32_e32 v44, 1.0, v44
	v_rcp_f32_e32 v44, v44
	s_nop 0
	v_mul_f32_e32 v40, v44, v40
	v_mul_f32_e32 v40, v45, v40
	v_cvt_pk_bf16_f32 v40, v39, v40
	v_lshlrev_b32_e32 v39, 16, v41
	v_mul_f32_e32 v44, 0xbfb8aa3b, v39
	v_exp_f32_e32 v44, v44
	v_and_b32_e32 v41, 0xffff0000, v41
	v_add_f32_e32 v44, 1.0, v44
	v_rcp_f32_e32 v44, v44
	s_nop 0
	v_mul_f32_e32 v39, v44, v39
	v_mul_f32_e32 v39, v42, v39
	v_mul_f32_e32 v42, 0xbfb8aa3b, v41
	v_exp_f32_e32 v42, v42
	v_pk_mul_f32 v[44:45], v[66:67], v[32:33] op_sel_hi:[1,0]
	v_add_f32_e32 v42, 1.0, v42
	v_rcp_f32_e32 v42, v42
	s_nop 0
	v_mul_f32_e32 v41, v42, v41
	v_mul_f32_e32 v41, v43, v41
	v_cvt_pk_bf16_f32 v41, v39, v41
	global_store_dwordx2 v[36:37], v[40:41], off
	global_load_dwordx2 v[40:41], v[34:35], off offset:2400
	v_pk_mul_f32 v[42:43], v[68:69], v[32:33] op_sel_hi:[1,0]
	s_waitcnt vmcnt(0) lgkmcnt(0)
	v_lshlrev_b32_e32 v39, 16, v40
	v_mul_f32_e32 v46, 0xbfb8aa3b, v39
	v_exp_f32_e32 v46, v46
	v_and_b32_e32 v40, 0xffff0000, v40
	v_add_f32_e32 v46, 1.0, v46
	v_rcp_f32_e32 v46, v46
	s_nop 0
	v_mul_f32_e32 v39, v46, v39
	v_mul_f32_e32 v39, v44, v39
	v_mul_f32_e32 v44, 0xbfb8aa3b, v40
	v_exp_f32_e32 v44, v44
	s_nop 0
	v_add_f32_e32 v44, 1.0, v44
	v_rcp_f32_e32 v44, v44
	s_nop 0
	v_mul_f32_e32 v40, v44, v40
	v_mul_f32_e32 v40, v45, v40
	v_cvt_pk_bf16_f32 v40, v39, v40
	v_lshlrev_b32_e32 v39, 16, v41
	v_mul_f32_e32 v44, 0xbfb8aa3b, v39
	v_exp_f32_e32 v44, v44
	v_and_b32_e32 v41, 0xffff0000, v41
	v_add_f32_e32 v44, 1.0, v44
	v_rcp_f32_e32 v44, v44
	s_nop 0
	v_mul_f32_e32 v39, v44, v39
	v_mul_f32_e32 v39, v42, v39
	v_mul_f32_e32 v42, 0xbfb8aa3b, v41
	v_exp_f32_e32 v42, v42
	s_nop 0
	v_add_f32_e32 v42, 1.0, v42
	v_rcp_f32_e32 v42, v42
	s_nop 0
	v_mul_f32_e32 v41, v42, v41
	v_mul_f32_e32 v41, v43, v41
	v_cvt_pk_bf16_f32 v41, v39, v41
	global_store_dwordx2 v[36:37], v[40:41], off offset:32
	global_load_dwordx2 v[40:41], v[34:35], off offset:2432
	s_waitcnt vmcnt(0) lgkmcnt(0)
	v_lshlrev_b32_e32 v39, 16, v40
	v_mul_f32_e32 v42, 0xbfb8aa3b, v39
	v_exp_f32_e32 v42, v42
	s_nop 0
	v_add_f32_e32 v42, 1.0, v42
	v_rcp_f32_e32 v42, v42
	s_nop 0
	v_mul_f32_e32 v39, v42, v39
	v_mul_f32_e32 v26, v26, v39
	v_and_b32_e32 v39, 0xffff0000, v40
	v_mul_f32_e32 v40, 0xbfb8aa3b, v39
	v_exp_f32_e32 v40, v40
	s_nop 0
	v_add_f32_e32 v40, 1.0, v40
	v_rcp_f32_e32 v40, v40
	s_nop 0
	v_mul_f32_e32 v39, v40, v39
	v_mul_f32_e32 v27, v27, v39
	v_cvt_pk_bf16_f32 v26, v26, v27
	v_lshlrev_b32_e32 v27, 16, v41
	v_mul_f32_e32 v39, 0xbfb8aa3b, v27
	v_exp_f32_e32 v39, v39
	s_nop 0
	v_add_f32_e32 v39, 1.0, v39
	v_rcp_f32_e32 v39, v39
	s_nop 0
	v_mul_f32_e32 v27, v39, v27
	v_mul_f32_e32 v27, v28, v27
	v_and_b32_e32 v28, 0xffff0000, v41
	v_mul_f32_e32 v39, 0xbfb8aa3b, v28
	v_exp_f32_e32 v39, v39
	s_nop 0
	v_add_f32_e32 v39, 1.0, v39
	v_rcp_f32_e32 v39, v39
	s_nop 0
	v_mul_f32_e32 v28, v39, v28
	v_mul_f32_e32 v28, v29, v28
	v_cvt_pk_bf16_f32 v27, v27, v28
	global_store_dwordx2 v[36:37], v[26:27], off offset:64
	global_load_dwordx2 v[26:27], v[34:35], off offset:2464
	s_waitcnt vmcnt(0) lgkmcnt(0)
	v_lshlrev_b32_e32 v28, 16, v26
	v_mul_f32_e32 v29, 0xbfb8aa3b, v28
	v_exp_f32_e32 v29, v29
	v_and_b32_e32 v26, 0xffff0000, v26
	v_add_f32_e32 v29, 1.0, v29
	v_rcp_f32_e32 v29, v29
	s_nop 0
	v_mul_f32_e32 v28, v29, v28
	v_mul_f32_e32 v22, v22, v28
	v_mul_f32_e32 v28, 0xbfb8aa3b, v26
	v_exp_f32_e32 v28, v28
	s_nop 0
	v_add_f32_e32 v28, 1.0, v28
	v_rcp_f32_e32 v28, v28
	s_nop 0
	v_mul_f32_e32 v26, v28, v26
	v_mul_f32_e32 v23, v23, v26
	v_cvt_pk_bf16_f32 v22, v22, v23
	v_lshlrev_b32_e32 v23, 16, v27
	v_mul_f32_e32 v26, 0xbfb8aa3b, v23
	v_exp_f32_e32 v26, v26
	s_nop 0
	v_add_f32_e32 v26, 1.0, v26
	v_rcp_f32_e32 v26, v26
	s_nop 0
	v_mul_f32_e32 v23, v26, v23
	v_mul_f32_e32 v23, v24, v23
	v_and_b32_e32 v24, 0xffff0000, v27
	v_mul_f32_e32 v26, 0xbfb8aa3b, v24
	v_exp_f32_e32 v26, v26
	s_nop 0
	v_add_f32_e32 v26, 1.0, v26
	v_rcp_f32_e32 v26, v26
	s_nop 0
	v_mul_f32_e32 v24, v26, v24
	v_mul_f32_e32 v24, v25, v24
	v_cvt_pk_bf16_f32 v23, v23, v24
	global_store_dwordx2 v[36:37], v[22:23], off offset:96
	ds_bpermute_b32 v22, v33, v89
	s_waitcnt lgkmcnt(0)
; __device__ __forceinline__ unsigned cvt_pk_bf16(float lo, float hi) { unsigned r; asm volatile("v_cvt_pk_bf16_f32 %0, %1, %2" : "=v"(r) : "v"(lo), "v"(hi)); return r; }
; __device__ __forceinline__ float bflo(unsigned w) { return __uint_as_float(w << 16); }
; __device__ __forceinline__ float bfhi(unsigned w) { return __uint_as_float(w & 0xffff0000u); }
; __device__ __forceinline__ float siluf(float x) { return x * __builtin_amdgcn_rcpf(1.f + __expf(-x)); }
; __device__ __forceinline__ void attn_unit(LAS unsigned char* lds, const bf16_t* QB, const bf16_t* KB, const bf16_t* VT, const bf16_t* P, bf16_t* Z0, int b, int h, int qrow0, int nkeys) {
;     ...
; #pragma unroll
;     for (int qb = 0; qb < 2; ++qb) {
;         float lt = lsum[qb]; lt += __shfl_xor(lt, 16); lt += __shfl_xor(lt, 32);
;         const float inv = 1.f / lt; const size_t row = (size_t)(qrow0 + wave * 32 + qb * 16 + fr);
; #pragma unroll
;         for (int db = 0; db < 4; ++db) { const int c4 = h * 64 + db * 16 + fq * 4; const u32x2 g = ld4(P + row * INP + OFF_GATE + c4);
;             const f32x4 v = o[qb][db] * inv; u32x2 w; w.x = cvt_pk_bf16(v[0] * siluf(bflo(g.x)), v[1] * siluf(bfhi(g.x))); w.y = cvt_pk_bf16(v[2] * siluf(bflo(g.y)), v[3] * siluf(bfhi(g.y)));
;             *(u32x2*)(Z0 + row * 256 + c4) = w; }
;     }
	v_add_f32_e32 v22, v89, v22
	ds_bpermute_b32 v23, v38, v22
	s_waitcnt lgkmcnt(0)
	v_add_f32_e32 v22, v22, v23
	v_div_scale_f32 v23, s[4:5], v22, v22, 1.0
	v_rcp_f32_e32 v24, v23
	s_nop 0
	v_fma_f32 v25, -v23, v24, 1.0
	v_fmac_f32_e32 v24, v25, v24
	v_div_scale_f32 v25, vcc, 1.0, v22, 1.0
	v_mul_f32_e32 v26, v25, v24
	v_fma_f32 v27, -v23, v26, v25
	v_fmac_f32_e32 v26, v27, v24
	v_fma_f32 v23, -v23, v26, v25
	v_div_fmas_f32 v23, v23, v24, v26
	v_mad_i64_i32 v[24:25], s[4:5], v86, s84, v[30:31]
	v_lshl_add_u64 v[24:25], v[24:25], 0, v[0:1]
	global_load_dwordx2 v[28:29], v[24:25], off offset:2368
	v_div_fixup_f32 v22, v23, v22, 1.0
	v_pk_mul_f32 v[20:21], v[20:21], v[22:23] op_sel_hi:[1,0]
	v_pk_mul_f32 v[18:19], v[18:19], v[22:23] op_sel_hi:[1,0]
	v_lshlrev_b64 v[26:27], 9, v[86:87]
	v_lshl_add_u64 v[26:27], s[44:45], 0, v[26:27]
	s_mov_b64 s[4:5], 0
	s_waitcnt vmcnt(0) lgkmcnt(0)
	v_lshlrev_b32_e32 v23, 16, v28
	v_mul_f32_e32 v30, 0xbfb8aa3b, v23
	v_exp_f32_e32 v30, v30
	s_nop 0
	v_add_f32_e32 v30, 1.0, v30
	v_rcp_f32_e32 v30, v30
	s_nop 0
	v_mul_f32_e32 v23, v30, v23
	v_mul_f32_e32 v18, v18, v23
	v_and_b32_e32 v23, 0xffff0000, v28
	v_mul_f32_e32 v28, 0xbfb8aa3b, v23
	v_exp_f32_e32 v28, v28
	s_nop 0
	v_add_f32_e32 v28, 1.0, v28
	v_rcp_f32_e32 v28, v28
	s_nop 0
	v_mul_f32_e32 v23, v28, v23
	v_mul_f32_e32 v19, v19, v23
	v_cvt_pk_bf16_f32 v28, v18, v19
	v_lshlrev_b32_e32 v18, 16, v29
	v_mul_f32_e32 v19, 0xbfb8aa3b, v18
	v_exp_f32_e32 v19, v19
	v_pk_mul_f32 v[16:17], v[16:17], v[22:23] op_sel_hi:[1,0]
	v_pk_mul_f32 v[14:15], v[14:15], v[22:23] op_sel_hi:[1,0]
	v_add_f32_e32 v19, 1.0, v19
	v_rcp_f32_e32 v19, v19
	s_nop 0
	v_mul_f32_e32 v18, v19, v18
	v_and_b32_e32 v19, 0xffff0000, v29
	v_mul_f32_e32 v18, v20, v18
	v_mul_f32_e32 v20, 0xbfb8aa3b, v19
	v_exp_f32_e32 v20, v20
	s_nop 0
	v_add_f32_e32 v20, 1.0, v20
	v_rcp_f32_e32 v20, v20
	s_nop 0
	v_mul_f32_e32 v19, v20, v19
	v_mul_f32_e32 v19, v21, v19
	v_cvt_pk_bf16_f32 v29, v18, v19
	global_load_dwordx2 v[20:21], v[24:25], off offset:2400
	v_lshl_add_u64 v[18:19], v[26:27], 0, v[0:1]
	global_store_dwordx2 v[18:19], v[28:29], off
	s_waitcnt vmcnt(0) lgkmcnt(0)
	v_lshlrev_b32_e32 v0, 16, v20
	v_mul_f32_e32 v23, 0xbfb8aa3b, v0
	v_exp_f32_e32 v23, v23
	s_nop 0
	v_add_f32_e32 v23, 1.0, v23
	v_rcp_f32_e32 v23, v23
	s_nop 0
	v_mul_f32_e32 v0, v23, v0
	v_mul_f32_e32 v0, v14, v0
	v_and_b32_e32 v14, 0xffff0000, v20
	v_mul_f32_e32 v20, 0xbfb8aa3b, v14
	v_exp_f32_e32 v20, v20
	v_pk_mul_f32 v[6:7], v[6:7], v[22:23] op_sel_hi:[1,0]
	v_pk_mul_f32 v[8:9], v[8:9], v[22:23] op_sel_hi:[1,0]
	v_pk_mul_f32 v[2:3], v[2:3], v[22:23] op_sel_hi:[1,0]
	v_add_f32_e32 v20, 1.0, v20
	v_rcp_f32_e32 v20, v20
	v_pk_mul_f32 v[4:5], v[4:5], v[22:23] op_sel_hi:[1,0]
	v_mul_f32_e32 v14, v20, v14
	v_mul_f32_e32 v14, v15, v14
	v_cvt_pk_bf16_f32 v14, v0, v14
	v_lshlrev_b32_e32 v0, 16, v21
	v_mul_f32_e32 v15, 0xbfb8aa3b, v0
	v_exp_f32_e32 v15, v15
	s_nop 0
	v_add_f32_e32 v15, 1.0, v15
	v_rcp_f32_e32 v15, v15
	s_nop 0
	v_mul_f32_e32 v0, v15, v0
	v_and_b32_e32 v15, 0xffff0000, v21
	v_mul_f32_e32 v0, v16, v0
	v_mul_f32_e32 v16, 0xbfb8aa3b, v15
	v_exp_f32_e32 v16, v16
	s_nop 0
	v_add_f32_e32 v16, 1.0, v16
	v_rcp_f32_e32 v16, v16
	s_nop 0
	v_mul_f32_e32 v15, v16, v15
	v_mul_f32_e32 v15, v17, v15
	v_cvt_pk_bf16_f32 v15, v0, v15
	global_store_dwordx2 v[18:19], v[14:15], off offset:32
	global_load_dwordx2 v[14:15], v[24:25], off offset:2432
	s_waitcnt vmcnt(0) lgkmcnt(0)
	v_lshlrev_b32_e32 v0, 16, v14
	v_mul_f32_e32 v16, 0xbfb8aa3b, v0
	v_exp_f32_e32 v16, v16
	s_nop 0
	v_add_f32_e32 v16, 1.0, v16
	v_rcp_f32_e32 v16, v16
	s_nop 0
	v_mul_f32_e32 v0, v16, v0
	v_mul_f32_e32 v0, v6, v0
	v_and_b32_e32 v6, 0xffff0000, v14
	v_mul_f32_e32 v14, 0xbfb8aa3b, v6
	v_exp_f32_e32 v14, v14
	s_nop 0
	v_add_f32_e32 v14, 1.0, v14
	v_rcp_f32_e32 v14, v14
	s_nop 0
	v_mul_f32_e32 v6, v14, v6
	v_mul_f32_e32 v6, v7, v6
	v_cvt_pk_bf16_f32 v6, v0, v6
	v_lshlrev_b32_e32 v0, 16, v15
	v_mul_f32_e32 v7, 0xbfb8aa3b, v0
	v_exp_f32_e32 v7, v7
	s_nop 0
	v_add_f32_e32 v7, 1.0, v7
	v_rcp_f32_e32 v7, v7
	s_nop 0
	v_mul_f32_e32 v0, v7, v0
	v_and_b32_e32 v7, 0xffff0000, v15
	v_mul_f32_e32 v0, v8, v0
	v_mul_f32_e32 v8, 0xbfb8aa3b, v7
	v_exp_f32_e32 v8, v8
	s_nop 0
	v_add_f32_e32 v8, 1.0, v8
	v_rcp_f32_e32 v8, v8
	s_nop 0
	v_mul_f32_e32 v7, v8, v7
	v_mul_f32_e32 v7, v9, v7
	v_cvt_pk_bf16_f32 v7, v0, v7
	global_store_dwordx2 v[18:19], v[6:7], off offset:64
	global_load_dwordx2 v[6:7], v[24:25], off offset:2464
	s_waitcnt vmcnt(0) lgkmcnt(0)
	v_lshlrev_b32_e32 v0, 16, v6
	v_mul_f32_e32 v8, 0xbfb8aa3b, v0
	v_exp_f32_e32 v8, v8
	s_nop 0
	v_add_f32_e32 v8, 1.0, v8
	v_rcp_f32_e32 v8, v8
	s_nop 0
	v_mul_f32_e32 v0, v8, v0
	v_mul_f32_e32 v0, v2, v0
	v_and_b32_e32 v2, 0xffff0000, v6
	v_mul_f32_e32 v6, 0xbfb8aa3b, v2
	v_exp_f32_e32 v6, v6
	s_nop 0
	v_add_f32_e32 v6, 1.0, v6
	v_rcp_f32_e32 v6, v6
	s_nop 0
	v_mul_f32_e32 v2, v6, v2
	v_mul_f32_e32 v2, v3, v2
	v_cvt_pk_bf16_f32 v2, v0, v2
	v_lshlrev_b32_e32 v0, 16, v7
	v_mul_f32_e32 v3, 0xbfb8aa3b, v0
	v_exp_f32_e32 v3, v3
	s_nop 0
	v_add_f32_e32 v3, 1.0, v3
	v_rcp_f32_e32 v3, v3
	s_nop 0
	v_mul_f32_e32 v0, v3, v0
	v_and_b32_e32 v3, 0xffff0000, v7
	v_mul_f32_e32 v0, v4, v0
	v_mul_f32_e32 v4, 0xbfb8aa3b, v3
	v_exp_f32_e32 v4, v4
	s_nop 0
	v_add_f32_e32 v4, 1.0, v4
	v_rcp_f32_e32 v4, v4
	s_nop 0
	v_mul_f32_e32 v3, v4, v3
	v_mul_f32_e32 v3, v5, v3
	v_cvt_pk_bf16_f32 v3, v0, v3
	global_store_dwordx2 v[18:19], v[2:3], off offset:96
; #define LAS __attribute__((address_space(3)))
; __device__ __forceinline__ int opaque_tid() { int t; asm volatile("v_mov_b32 %0, %1" : "=v"(t) : "v"((int)threadIdx.x)); return t; }
; #define ATT_LOAD(S_, tt) do { const bf16_t* kt_ = kg + (size_t)(tt) * 64 * 96; rk0[S_] = ld8(kt_ + kp0 * 8); if (kp1 < 768) rk1[S_] = ld8(kt_ + kp1 * 8); rv[S_] = ld8(vg + (size_t)vd * NKEY + (tt) * 64 + vpart * 8); } while (0)
; #define ATT_STORE(S_, bufi) do { LAS unsigned char* kb_ = lds + (bufi) * KBUF; *(LAS u32x4*)(kb_ + (kp0 / 12) * KST + (kp0 % 12) * 16) = rk0[S_]; if (kp1 < 768) *(LAS u32x4*)(kb_ + (kp1 / 12) * KST + (kp1 % 12) * 16) = rk1[S_]; \
;         *(LAS u32x4*)(lds + VOFF + (bufi) * VBUF + vd * VST + vpart * 16) = rv[S_]; } while (0)
; __device__ __forceinline__ void attn_unit(LAS unsigned char* lds, const bf16_t* QB, const bf16_t* KB, const bf16_t* VT, const bf16_t* P, bf16_t* Z0, int b, int h, int qrow0, int nkeys) {
;     const int tid = opaque_tid(), lane = tid & 63, wave = tid >> 6, fr = lane & 15, fq = lane >> 4;
;     constexpr int KST = 208, VST = 144, KBUF = 64 * KST, VBUF = 64 * VST, VOFF = 2 * KBUF;
;     bf16x8 qf[2][3];
; #pragma unroll
;     for (int qb = 0; qb < 2; ++qb)
; #pragma unroll
;         for (int ks = 0; ks < 3; ++ks) qf[qb][ks] = asfrag(ld8(QB + (size_t)(qrow0 + wave * 32 + qb * 16 + fr) * 384 + h * 96 + ks * 32 + fq * 8));
;     const bf16_t* kg = KB + (size_t)(b * 4 + h) * NKEY * 96;
;     const bf16_t* vg = VT + (size_t)(b * 4 + h) * 64 * NKEY;
;     const int kp0 = tid, kp1 = tid + 512;
;     const int vd = tid >> 3, vpart = tid & 7;
;     u32x4 rk0[2], rk1[2], rv[2];
;     const int ntile = nkeys >> 6;
;     ...
;     __syncthreads();
;     ATT_LOAD(0, 0); ATT_STORE(0, 0);
;     __syncthreads();
;     if (1 < ntile) ATT_LOAD(0, 1);
;     if (2 < ntile) ATT_LOAD(1, 2);
; __global__ void __launch_bounds__(512, 2) fwd_kernel(KArgs a) {
;     ...
;             for (int u = bid; u < 256 + (wctx ? 32 : 0); u += G) {
;                 if (u < 256) { const int us = G == 256 ? (u & 7) * 32 + (u >> 3) : u;
;                     const int qb = us & 7, h = (us >> 3) & 3, b = us >> 5; attn_unit(lds, QB, KB, VT, P, Z0, b, h, b * 2048 + qb * 256, NKEY); }
.LBB0_1036:
	s_movk_i32 s18, 0xe0
	s_and_b64 vcc, exec, s[4:5]
	s_cbranch_vccz .LBB0_1009
	s_lshl_b32 s1, s46, 5
	s_and_b32 s1, s1, 0xe0
	s_ashr_i32 s4, s46, 3
	s_add_i32 s1, s1, s4
	v_readlane_b32 s4, v253, 25
	v_readlane_b32 s5, v253, 26
	s_and_b64 s[4:5], s[4:5], exec
	s_cselect_b32 s4, s1, s46
	s_bfe_u32 s1, s4, 0x20003
	s_ashr_i32 s6, s4, 5
	s_lshl_b32 s4, s4, 8
	s_lshl_b32 s5, s6, 11
	s_and_b32 s4, s4, 0x700
	s_or_b32 s4, s5, s4
	v_mov_b32 v29, v194
	v_mov_b32_e32 v6, v1
	v_and_b32_e32 v32, 15, v29
	v_ashrrev_i32_e32 v0, 1, v29
	v_or_b32_e32 v2, s4, v32
	s_mul_i32 s4, s1, 0xc0
	v_bfe_u32 v170, v29, 4, 2
	v_and_b32_e32 v0, 0xffffffe0, v0
	s_add_u32 s4, s28, s4
	v_add_u32_e32 v90, v2, v0
	s_addc_u32 s5, s29, 0
	v_lshlrev_b32_e32 v0, 4, v170
	v_lshl_add_u64 v[2:3], s[4:5], 0, v[0:1]
	v_or_b32_e32 v86, 16, v90
	v_mad_i64_i32 v[4:5], s[4:5], v90, s50, v[2:3]
	v_mad_i64_i32 v[2:3], s[4:5], v86, s50, v[2:3]
	s_lshl_b32 s4, s6, 2
	s_or_b32 s6, s4, s1
	s_mul_i32 s4, s6, 0x6c000
	s_mul_hi_i32 s5, s6, 0x6c000
	s_add_u32 s22, s30, s4
	v_lshlrev_b32_e32 v26, 3, v29
	global_load_dwordx4 v[34:37], v[4:5], off
	global_load_dwordx4 v[38:41], v[4:5], off offset:64
	global_load_dwordx4 v[42:45], v[4:5], off offset:128
	global_load_dwordx4 v[46:49], v[2:3], off
	global_load_dwordx4 v[50:53], v[2:3], off offset:64
	global_load_dwordx4 v[54:57], v[2:3], off offset:128
	s_addc_u32 s23, s31, s5
	v_ashrrev_i32_e32 v27, 31, v26
	v_lshl_add_u64 v[2:3], v[26:27], 1, s[22:23]
	s_waitcnt lgkmcnt(0)
	s_barrier
	global_load_dwordx4 v[14:17], v[2:3], off
	v_mov_b32_e32 v2, v1
	v_mov_b32_e32 v3, v1
	v_mov_b32_e32 v4, v1
	v_mov_b32_e32 v5, v1
	v_mov_b32_e32 v7, v1
	v_add_u32_e32 v33, 0x200, v29
	s_movk_i32 s7, 0xff
	v_mov_b32_e32 v0, v1
	v_mov_b64_e32 v[8:9], v[6:7]
	v_cmp_lt_i32_e32 vcc, s7, v29
	v_cmp_gt_i32_e64 s[36:37], s14, v29
	v_mov_b32_e32 v18, 0
	v_lshlrev_b32_e32 v28, 3, v33
	v_mov_b64_e32 v[6:7], v[4:5]
	v_mov_b64_e32 v[4:5], v[2:3]
	v_mov_b64_e32 v[2:3], v[0:1]
	v_mov_b32_e32 v19, 0
	v_mov_b32_e32 v20, 0
	v_mov_b32_e32 v21, 0
	s_and_saveexec_b64 s[20:21], s[36:37]
	s_cbranch_execz .LBB0_1039
	v_lshlrev_b32_e32 v2, 3, v33
	v_ashrrev_i32_e32 v3, 31, v2
	v_lshl_add_u64 v[2:3], v[2:3], 1, s[22:23]
	global_load_dwordx4 v[2:5], v[2:3], off
	v_mov_b32_e32 v6, v1
	v_mov_b32_e32 v7, v1
	v_mov_b32_e32 v8, v1
	v_mov_b32_e32 v9, v1
	s_waitcnt vmcnt(0) lgkmcnt(0)
	v_mov_b32_e32 v18, v2
	v_mov_b32_e32 v19, v3
	v_mov_b32_e32 v20, v4
	v_mov_b32_e32 v21, v5
.LBB0_1039:
	s_or_b64 exec, exec, s[20:21]
	s_mul_i32 s20, s6, 0x48000
	s_mul_hi_i32 s21, s6, 0x48000
	s_add_u32 s6, s34, s20
	s_addc_u32 s7, s35, s21
	v_ashrrev_i32_e32 v58, 3, v29
	v_and_b32_e32 v0, 7, v29
	v_mov_b64_e32 v[22:23], s[6:7]
	v_mad_i64_i32 v[22:23], s[6:7], v58, s88, v[22:23]
	v_lshlrev_b32_e32 v0, 4, v0
	v_lshl_add_u64 v[30:31], v[22:23], 0, v[0:1]
	global_load_dwordx4 v[22:25], v[30:31], off
	s_mov_b32 s6, 0x2aaaaaab
	v_mul_hi_i32 v59, v29, s6
	v_lshrrev_b32_e32 v60, 31, v59
	v_ashrrev_i32_e32 v59, 1, v59
	v_add_u32_e32 v59, v59, v60
	v_mul_lo_u32 v60, v59, s18
	v_mul_lo_u32 v59, v59, 12
	v_sub_u32_e32 v29, v29, v59
	v_add_u32_e32 v60, 0, v60
	v_lshlrev_b32_e32 v29, 4, v29
	v_add_u32_e32 v171, v60, v29
	s_waitcnt vmcnt(0) lgkmcnt(0)
	ds_write_b128 v171, v[14:17]
	v_mul_hi_i32 v15, v33, s6
	v_lshrrev_b32_e32 v14, 31, v15
	v_ashrrev_i32_e32 v15, 1, v15
	s_and_saveexec_b64 s[24:25], s[36:37]
	s_cbranch_execz .LBB0_1041
	v_add_u32_e32 v16, v15, v14
	v_mul_lo_u32 v17, v16, s18
	v_mul_lo_u32 v16, v16, 12
	v_sub_u32_e32 v16, v33, v16
	v_lshlrev_b32_e32 v16, 4, v16
	v_add3_u32 v16, 0, v17, v16
	ds_write_b128 v16, v[18:21]

; #define LAS __attribute__((address_space(3)))
; __device__ __forceinline__ bf16_t tobf(float f) { return (bf16_t)(cvt_pk_bf16(f, 0.f) & 0xffffu); }
; #define MFMA16(a, b, c) __builtin_amdgcn_mfma_f32_16x16x32_bf16((a), (b), (c), 0, 0, 0)
; #define S5_LOAD(rb_) do { _Pragma("unroll") for (int j_ = 0; j_ < 3; ++j_) { const int p_ = tid + j_ * 512, rr_ = p_ / 96, kc_ = p_ % 96, r_ = (rb_) * 16 + rr_; \
;         st[j_] = kc_ < 64 ? ld8(P + (size_t)(tokbase_of(r_) + (kc_ >> 1)) * INP + OFF_S5 + g * 16 + (kc_ & 1) * 8) : ld8(S5H + ((size_t)r_ * 16 + g) * 256 + (kc_ - 64) * 8); } } while (0)
; #define S5_STORE(buf_) do { _Pragma("unroll") for (int j_ = 0; j_ < 3; ++j_) { const int p_ = tid + j_ * 512, rr_ = p_ / 96, kc_ = p_ % 96; *(LAS u32x4*)(lds + (buf_) * BUF + rr_ * RST + kc_ * 16) = st[j_]; } } while (0)
; #define S5_LOAD(rb_) do { _Pragma("unroll") for (int j_ = 0; j_ < 2; ++j_) { const int p_ = tid + j_ * 512, rr_ = p_ >> 6, kc_ = p_ & 63, r_ = (rb_) * 16 + rr_; \
;         st[j_] = ld8(P + (size_t)(tokbase_of(r_) + (kc_ >> 1)) * INP + OFF_S5 + g * 16 + (kc_ & 1) * 8); } } while (0)
; #define S5_STORE(buf_) do { _Pragma("unroll") for (int j_ = 0; j_ < 2; ++j_) { const int p_ = tid + j_ * 512, rr_ = p_ >> 6, kc_ = p_ & 63; *(LAS u32x4*)(lds + (buf_) * BUF + rr_ * RST + kc_ * 16) = st[j_]; } } while (0)
; __device__ __forceinline__ void s5_pass2_block(LAS unsigned char* lds, int bt, int l, const bf16_t* P, const bf16_t* BM2, const bf16_t* S5H, bf16_t* YB) {
;     ...
;     for (int i = 0; i < 9; ++i) {
;         const int rb = rg * 9 + i;
;         S5_STORE(i & 1);
;         __syncthreads();
;         if (i < 8) S5_LOAD(rb + 1);
;         const LAS unsigned char* ab = lds + (i & 1) * BUF + fr * RST + fq * 16;
;         f32x4 acc = (f32x4){0.f, 0.f, 0.f, 0.f};
; #pragma unroll
;         for (int ks = 0; ks < 24; ++ks) acc = MFMA16(*(const LAS bf16x8*)(ab + ks * 64), bw[ks], acc);
; #pragma unroll
;         for (int q = 0; q < 4; ++q) YB[(size_t)(tokbase_of(rb * 16 + fq * 4 + q) + cb) * 256 + g * 16 + fr] = tobf(acc[q]);
;     }
.LBB0_1116:
	v_add3_u32 v0, 0, v140, v120
	s_waitcnt vmcnt(0)
	ds_write_b128 v0, v[102:105]
	v_add3_u32 v0, 0, v139, v122
	ds_write_b128 v0, v[106:109]
	v_add3_u32 v0, 0, v138, v124
	ds_write_b128 v0, v[110:113]
	s_waitcnt lgkmcnt(0)
	s_barrier
	ds_read_b128 v[102:105], v123
	s_addk_i32 s31, 0x80
	v_or_b32_e32 v0, s31, v121
	s_waitcnt lgkmcnt(0)
	v_mfma_f32_16x16x32_bf16 v[98:101], v[102:105], v[98:101], 0
	ds_read_b128 v[102:105], v123 offset:64
	s_add_i32 s19, s19, s74
	s_cmpk_gt_i32 s19, 0xff
	s_waitcnt lgkmcnt(0)
	v_mfma_f32_16x16x32_bf16 v[94:97], v[102:105], v[94:97], v[98:101]
	s_nop 2
	ds_read_b128 v[98:101], v123 offset:128
	s_waitcnt lgkmcnt(0)
	v_mfma_f32_16x16x32_bf16 v[90:93], v[98:101], v[90:93], v[94:97]
	s_nop 2
	ds_read_b128 v[94:97], v123 offset:192
	s_waitcnt lgkmcnt(0)
	v_mfma_f32_16x16x32_bf16 v[86:89], v[94:97], v[86:89], v[90:93]
	s_nop 2
	ds_read_b128 v[90:93], v123 offset:256
	s_waitcnt lgkmcnt(0)
	v_mfma_f32_16x16x32_bf16 v[82:85], v[90:93], v[82:85], v[86:89]
	s_nop 2
	ds_read_b128 v[86:89], v123 offset:320
	s_waitcnt lgkmcnt(0)
	v_mfma_f32_16x16x32_bf16 v[78:81], v[86:89], v[78:81], v[82:85]
	s_nop 2
	ds_read_b128 v[82:85], v123 offset:384
	s_waitcnt lgkmcnt(0)
	v_mfma_f32_16x16x32_bf16 v[74:77], v[82:85], v[74:77], v[78:81]
	s_nop 2
	ds_read_b128 v[78:81], v123 offset:448
	s_waitcnt lgkmcnt(0)
	v_mfma_f32_16x16x32_bf16 v[70:73], v[78:81], v[70:73], v[74:77]
	s_nop 2
	ds_read_b128 v[74:77], v123 offset:512
	s_waitcnt lgkmcnt(0)
	v_mfma_f32_16x16x32_bf16 v[66:69], v[74:77], v[66:69], v[70:73]
	s_nop 2
	ds_read_b128 v[70:73], v123 offset:576
	s_waitcnt lgkmcnt(0)
	v_mfma_f32_16x16x32_bf16 v[62:65], v[70:73], v[62:65], v[66:69]
	s_nop 2
	ds_read_b128 v[66:69], v123 offset:640
	s_waitcnt lgkmcnt(0)
	v_mfma_f32_16x16x32_bf16 v[58:61], v[66:69], v[58:61], v[62:65]
	s_nop 2
	ds_read_b128 v[62:65], v123 offset:704
	s_waitcnt lgkmcnt(0)
	v_mfma_f32_16x16x32_bf16 v[54:57], v[62:65], v[54:57], v[58:61]
	s_nop 2
	ds_read_b128 v[58:61], v123 offset:768
	s_waitcnt lgkmcnt(0)
	v_mfma_f32_16x16x32_bf16 v[50:53], v[58:61], v[50:53], v[54:57]
	s_nop 2
	ds_read_b128 v[54:57], v123 offset:832
	s_waitcnt lgkmcnt(0)
	v_mfma_f32_16x16x32_bf16 v[46:49], v[54:57], v[46:49], v[50:53]
	s_nop 2
	ds_read_b128 v[50:53], v123 offset:896
	s_waitcnt lgkmcnt(0)
	v_mfma_f32_16x16x32_bf16 v[42:45], v[50:53], v[42:45], v[46:49]
	s_nop 2
	ds_read_b128 v[46:49], v123 offset:960
	s_waitcnt lgkmcnt(0)
	v_mfma_f32_16x16x32_bf16 v[38:41], v[46:49], v[38:41], v[42:45]
	s_nop 2
	ds_read_b128 v[42:45], v123 offset:1024
	s_waitcnt lgkmcnt(0)
	v_mfma_f32_16x16x32_bf16 v[34:37], v[42:45], v[34:37], v[38:41]
	s_nop 2
	ds_read_b128 v[38:41], v123 offset:1088
	s_waitcnt lgkmcnt(0)
	v_mfma_f32_16x16x32_bf16 v[30:33], v[38:41], v[30:33], v[34:37]
	s_nop 2
	ds_read_b128 v[34:37], v123 offset:1152
	s_waitcnt lgkmcnt(0)
	v_mfma_f32_16x16x32_bf16 v[26:29], v[34:37], v[26:29], v[30:33]
	s_nop 2
	ds_read_b128 v[30:33], v123 offset:1216
	s_waitcnt lgkmcnt(0)
	v_mfma_f32_16x16x32_bf16 v[22:25], v[30:33], v[22:25], v[26:29]
	s_nop 2
	ds_read_b128 v[26:29], v123 offset:1280
	s_waitcnt lgkmcnt(0)
	v_mfma_f32_16x16x32_bf16 v[18:21], v[26:29], v[18:21], v[22:25]
	s_nop 2
	ds_read_b128 v[22:25], v123 offset:1344
	s_waitcnt lgkmcnt(0)
	v_mfma_f32_16x16x32_bf16 v[14:17], v[22:25], v[14:17], v[18:21]
	s_nop 2
	ds_read_b128 v[18:21], v123 offset:1408
	s_waitcnt lgkmcnt(0)
	v_mfma_f32_16x16x32_bf16 v[6:9], v[18:21], v[6:9], v[14:17]
	s_nop 2
	ds_read_b128 v[14:17], v123 offset:1472
	s_waitcnt lgkmcnt(0)
	v_mfma_f32_16x16x32_bf16 v[2:5], v[14:17], v[2:5], v[6:9]
	s_nop 2
	v_mul_hi_u32 v6, v0, s94
	v_lshrrev_b32_e32 v6, 4, v6
	v_lshl_add_u32 v8, v6, 11, v210
	v_lshl_or_b32 v9, v6, 8, v211
	v_mul_lo_u32 v6, v6, s85
	v_sub_u32_e32 v6, v0, v6
	v_cmp_gt_u32_e32 vcc, 8, v6
	v_lshlrev_b32_e32 v6, 5, v6
	v_or_b32_e32 v7, v9, v6
	v_add_u32_e32 v6, v8, v6
	v_cndmask_b32_e32 v6, v6, v7, vcc
	v_add_u32_e32 v6, s30, v6
	v_ashrrev_i32_e32 v7, 31, v6
	v_lshlrev_b64 v[6:7], 9, v[6:7]
	v_cvt_pk_bf16_f32 v2, v2, v1
	v_lshl_add_u64 v[6:7], v[118:119], 0, v[6:7]
	global_store_short v[6:7], v2, off
	v_or_b32_e32 v2, 1, v0
	v_cvt_pk_bf16_f32 v6, v3, v1
	v_mul_hi_u32 v3, v2, s52
	v_mul_u32_u24_e32 v3, 0x48, v3
	v_sub_u32_e32 v2, v2, v3
	v_cmp_gt_u32_e32 vcc, 8, v2
	v_lshlrev_b32_e32 v2, 5, v2
	v_or_b32_e32 v3, v2, v9
	v_add_u32_e32 v2, v8, v2
	v_cndmask_b32_e32 v2, v2, v3, vcc
	v_add_u32_e32 v2, s30, v2
	v_ashrrev_i32_e32 v3, 31, v2
	v_lshlrev_b64 v[2:3], 9, v[2:3]
	v_lshl_add_u64 v[2:3], v[118:119], 0, v[2:3]
	global_store_short v[2:3], v6, off
	v_or_b32_e32 v2, 2, v0
	v_mul_hi_u32 v3, v2, s52
	v_mul_u32_u24_e32 v3, 0x48, v3
	v_sub_u32_e32 v2, v2, v3
	v_cmp_gt_u32_e32 vcc, 8, v2
	v_lshlrev_b32_e32 v2, 5, v2
	v_or_b32_e32 v3, v2, v9
	v_add_u32_e32 v2, v8, v2
	v_cndmask_b32_e32 v2, v2, v3, vcc
	v_add_u32_e32 v2, s30, v2
	v_ashrrev_i32_e32 v3, 31, v2
	v_lshlrev_b64 v[2:3], 9, v[2:3]
	v_lshl_add_u64 v[2:3], v[118:119], 0, v[2:3]
	v_or_b32_e32 v0, 3, v0
	v_cvt_pk_bf16_f32 v4, v4, v1
	global_store_short v[2:3], v4, off
	v_mul_hi_u32 v2, v0, s52
	v_mul_u32_u24_e32 v2, 0x48, v2
	v_sub_u32_e32 v0, v0, v2
	v_cmp_gt_u32_e32 vcc, 8, v0
	v_lshlrev_b32_e32 v0, 5, v0
	v_or_b32_e32 v2, v0, v9
	v_add_u32_e32 v0, v8, v0
	v_cndmask_b32_e32 v0, v0, v2, vcc
	v_add_u32_e32 v2, s30, v0
	v_ashrrev_i32_e32 v3, 31, v2
	v_lshlrev_b64 v[2:3], 9, v[2:3]
	v_lshl_add_u64 v[2:3], v[118:119], 0, v[2:3]
	v_cvt_pk_bf16_f32 v4, v5, v1
	global_store_short v[2:3], v4, off
	s_waitcnt lgkmcnt(0)
	s_barrier
	s_cbranch_scc1 .LBB0_1161
; #define LAS __attribute__((address_space(3)))
; __device__ __forceinline__ int opaque_tid() { int t; asm volatile("v_mov_b32 %0, %1" : "=v"(t) : "v"((int)threadIdx.x)); return t; }
; #define S5_LOAD(rb_) do { _Pragma("unroll") for (int j_ = 0; j_ < 3; ++j_) { const int p_ = tid + j_ * 512, rr_ = p_ / 96, kc_ = p_ % 96, r_ = (rb_) * 16 + rr_; \
;         st[j_] = kc_ < 64 ? ld8(P + (size_t)(tokbase_of(r_) + (kc_ >> 1)) * INP + OFF_S5 + g * 16 + (kc_ & 1) * 8) : ld8(S5H + ((size_t)r_ * 16 + g) * 256 + (kc_ - 64) * 8); } } while (0)
; #define S5_LOAD(rb_) do { _Pragma("unroll") for (int j_ = 0; j_ < 2; ++j_) { const int p_ = tid + j_ * 512, rr_ = p_ >> 6, kc_ = p_ & 63, r_ = (rb_) * 16 + rr_; \
;         st[j_] = ld8(P + (size_t)(tokbase_of(r_) + (kc_ >> 1)) * INP + OFF_S5 + g * 16 + (kc_ & 1) * 8); } } while (0)
; #define WSL unsigned char* wsl = a.ws; asm volatile("" : "+s"(wsl))
; __device__ __forceinline__ void s5_pass2_block(LAS unsigned char* lds, int bt, int l, const bf16_t* P, const bf16_t* BM2, const bf16_t* S5H, bf16_t* YB) {
;     const int tid = opaque_tid(), lane = tid & 63, wave = __builtin_amdgcn_readfirstlane(tid >> 6), fr = lane & 15, fq = lane >> 4;
;     const int cq = bt & 3, rg = (bt >> 2) & 3, g = bt >> 4, cb = cq * 8 + wave;
;     constexpr int RST = 1552, BUF = 16 * RST;
;     bf16x8 bw[24];
;     const bf16_t* bp = BM2 + ((size_t)(l * 16 + g) * 512 + cb * 16 + fr) * 768 + fq * 8;
; #pragma unroll
;     for (int ks = 0; ks < 24; ++ks) bw[ks] = asfrag(ld8(bp + ks * 32));
;     u32x4 st[3];
;     ...
;     __syncthreads();
;     S5_LOAD(rg * 9);
; __global__ void __launch_bounds__(512, 2) fwd_kernel(KArgs a) {
;     ...
;             { WSL; for (int bt = bid; bt < 256; bt += G) s5_pass2_block(lds, G == 256 ? (bt & 7) * 32 + (bt >> 3) : bt, l, P, BM2, S5H, YB); }
.LBB0_1117:
	s_lshl_b32 s14, s19, 5
	s_and_b32 s14, s14, 0xe0
	s_ashr_i32 s15, s19, 3
	s_add_i32 s14, s14, s15
	s_and_b64 s[20:21], s[46:47], exec
	s_cselect_b32 s28, s14, s19
	v_mov_b32 v110, v194
	s_ashr_i32 s20, s28, 4
	v_readfirstlane_b32 s14, v110
	s_ashr_i32 s30, s14, 6
	s_lshl_b32 s14, s28, 3
	s_and_b32 s14, s14, 24
	s_add_i32 s30, s30, s14
	v_readlane_b32 s14, v254, 35
	s_add_i32 s22, s20, s14
	s_ashr_i32 s23, s22, 31
	s_lshl_b32 s14, s30, 4
	s_lshl_b64 s[22:23], s[22:23], 9
	s_ashr_i32 s15, s14, 31
	v_and_b32_e32 v118, 15, v110
	s_add_u32 s14, s22, s14
	v_or_b32_e32 v0, s14, v118
	v_mov_b64_e32 v[2:3], s[42:43]
	v_bfe_u32 v136, v110, 4, 2
	s_addc_u32 s15, s23, s15
	v_mad_u64_u32 v[2:3], s[22:23], v0, s49, v[2:3]
	v_mad_i32_i24 v3, s15, v209, v3
	v_lshlrev_b32_e32 v0, 4, v136
	v_lshl_add_u64 v[2:3], v[2:3], 0, v[0:1]
	global_load_dwordx4 v[98:101], v[2:3], off
	global_load_dwordx4 v[94:97], v[2:3], off offset:64
	global_load_dwordx4 v[90:93], v[2:3], off offset:128
	global_load_dwordx4 v[86:89], v[2:3], off offset:192
	global_load_dwordx4 v[82:85], v[2:3], off offset:256
	global_load_dwordx4 v[78:81], v[2:3], off offset:320
	global_load_dwordx4 v[74:77], v[2:3], off offset:384
	global_load_dwordx4 v[70:73], v[2:3], off offset:448
	global_load_dwordx4 v[66:69], v[2:3], off offset:512
	global_load_dwordx4 v[62:65], v[2:3], off offset:576
	global_load_dwordx4 v[58:61], v[2:3], off offset:640
	global_load_dwordx4 v[54:57], v[2:3], off offset:704
	global_load_dwordx4 v[50:53], v[2:3], off offset:768
	global_load_dwordx4 v[46:49], v[2:3], off offset:832
	global_load_dwordx4 v[42:45], v[2:3], off offset:896
	global_load_dwordx4 v[38:41], v[2:3], off offset:960
	global_load_dwordx4 v[34:37], v[2:3], off offset:1024
	global_load_dwordx4 v[30:33], v[2:3], off offset:1088
	global_load_dwordx4 v[26:29], v[2:3], off offset:1152
	global_load_dwordx4 v[22:25], v[2:3], off offset:1216
	global_load_dwordx4 v[18:21], v[2:3], off offset:1280
	global_load_dwordx4 v[14:17], v[2:3], off offset:1344
	global_load_dwordx4 v[6:9], v[2:3], off offset:1408
	s_nop 0
	global_load_dwordx4 v[2:5], v[2:3], off offset:1472
	v_mul_hi_i32 v102, v110, s50
	v_lshrrev_b32_e32 v103, 31, v102
	v_ashrrev_i32_e32 v102, 4, v102
	s_bfe_u32 s33, s28, 0x20002
	s_ashr_i32 s21, s20, 31
	v_add_u32_e32 v137, v102, v103
	s_mul_i32 s31, s33, 0x90
	s_lshl_b64 s[20:21], s[20:21], 9
	v_mul_lo_u32 v102, v137, s48
	s_add_u32 s24, s1, s20
	v_sub_u32_e32 v126, v110, v102
	v_add_u32_e32 v114, s31, v137
	s_addc_u32 s25, s6, s21
	v_cmp_gt_i32_e32 vcc, 64, v126
	v_cmp_lt_i32_e64 s[36:37], 63, v126
	v_ashrrev_i32_e32 v115, 31, v114
	v_lshlrev_b32_e32 v120, 4, v126
	s_waitcnt lgkmcnt(0)
	s_barrier
	s_and_saveexec_b64 s[22:23], s[36:37]
	s_xor_b64 s[22:23], exec, s[22:23]
	v_lshlrev_b64 v[102:103], 13, v[114:115]
	v_lshl_add_u64 v[102:103], s[24:25], 0, v[102:103]
	v_mov_b32_e32 v121, v1
	v_lshl_add_u64 v[102:103], v[102:103], 0, v[120:121]
	v_lshl_add_u64 v[102:103], v[102:103], 0, s[54:55]
	s_or_saveexec_b64 s[26:27], s[22:23]
	s_and_b32 s22, s28, -16
	s_ashr_i32 s23, s22, 31
	s_xor_b64 exec, exec, s[26:27]
	s_cbranch_execz .LBB0_1125
	v_mul_hi_i32 v102, v114, s94
	v_lshrrev_b32_e32 v103, 31, v102
	v_ashrrev_i32_e32 v102, 4, v102
	v_add_u32_e32 v103, v102, v103
	v_mul_lo_u32 v102, v103, s85
	v_sub_u32_e32 v102, v114, v102
	v_cmp_lt_i32_e64 s[36:37], 7, v102
	v_lshlrev_b32_e32 v104, 5, v102
	s_and_saveexec_b64 s[28:29], s[36:37]
	s_xor_b64 s[28:29], exec, s[28:29]
	v_lshlrev_b32_e32 v102, 11, v103
	v_add3_u32 v102, v104, v102, s95
	s_andn2_saveexec_b64 s[28:29], s[28:29]
	v_lshlrev_b32_e32 v102, 8, v103
	v_add3_u32 v102, v102, v104, s0
	s_or_b64 exec, exec, s[28:29]
	v_ashrrev_i32_e32 v103, 1, v126
	v_add_u32_e32 v104, v102, v103
	v_mov_b64_e32 v[102:103], s[4:5]
	v_mad_i64_i32 v[102:103], s[28:29], v104, s84, v[102:103]
	v_lshl_add_u64 v[102:103], s[22:23], 1, v[102:103]
	v_and_b32_e32 v104, 16, v120
	v_mov_b32_e32 v105, v1
	v_lshl_add_u64 v[102:103], v[102:103], 0, v[104:105]
	v_lshl_add_u64 v[102:103], v[102:103], 0, s[56:57]
; #define LAS __attribute__((address_space(3)))
; #define S5_LOAD(rb_) do { _Pragma("unroll") for (int j_ = 0; j_ < 3; ++j_) { const int p_ = tid + j_ * 512, rr_ = p_ / 96, kc_ = p_ % 96, r_ = (rb_) * 16 + rr_; \
;         st[j_] = kc_ < 64 ? ld8(P + (size_t)(tokbase_of(r_) + (kc_ >> 1)) * INP + OFF_S5 + g * 16 + (kc_ & 1) * 8) : ld8(S5H + ((size_t)r_ * 16 + g) * 256 + (kc_ - 64) * 8); } } while (0)
; #define S5_STORE(buf_) do { _Pragma("unroll") for (int j_ = 0; j_ < 3; ++j_) { const int p_ = tid + j_ * 512, rr_ = p_ / 96, kc_ = p_ % 96; *(LAS u32x4*)(lds + (buf_) * BUF + rr_ * RST + kc_ * 16) = st[j_]; } } while (0)
; #define S5_LOAD(rb_) do { _Pragma("unroll") for (int j_ = 0; j_ < 2; ++j_) { const int p_ = tid + j_ * 512, rr_ = p_ >> 6, kc_ = p_ & 63, r_ = (rb_) * 16 + rr_; \
;         st[j_] = ld8(P + (size_t)(tokbase_of(r_) + (kc_ >> 1)) * INP + OFF_S5 + g * 16 + (kc_ & 1) * 8); } } while (0)
; #define S5_STORE(buf_) do { _Pragma("unroll") for (int j_ = 0; j_ < 2; ++j_) { const int p_ = tid + j_ * 512, rr_ = p_ >> 6, kc_ = p_ & 63; *(LAS u32x4*)(lds + (buf_) * BUF + rr_ * RST + kc_ * 16) = st[j_]; } } while (0)
; __device__ __forceinline__ void s5_pass2_block(LAS unsigned char* lds, int bt, int l, const bf16_t* P, const bf16_t* BM2, const bf16_t* S5H, bf16_t* YB) {
;     ...
;     u32x4 st[3];
;     ...
;     __syncthreads();
;     S5_LOAD(rg * 9);
;     for (int i = 0; i < 9; ++i) {
;         const int rb = rg * 9 + i;
;         S5_STORE(i & 1);
;         __syncthreads();
;         if (i < 8) S5_LOAD(rb + 1);
;         const LAS unsigned char* ab = lds + (i & 1) * BUF + fr * RST + fq * 16;
.LBB0_1125:
	s_or_b64 exec, exec, s[26:27]
	global_load_dwordx4 v[102:105], v[102:103], off
	v_add_u32_e32 v106, 0x200, v110
	v_mul_hi_i32 v107, v106, s50
	v_lshrrev_b32_e32 v108, 31, v107
	v_ashrrev_i32_e32 v107, 4, v107
	v_add_u32_e32 v149, v107, v108
	v_mul_lo_u32 v107, v149, s48
	v_sub_u32_e32 v127, v106, v107
	v_add_u32_e32 v116, s31, v149
	v_cmp_gt_i32_e64 s[36:37], 64, v127
	v_cmp_lt_i32_e64 s[38:39], 63, v127
	v_ashrrev_i32_e32 v117, 31, v116
	v_lshlrev_b32_e32 v122, 4, v127
	s_and_saveexec_b64 s[26:27], s[38:39]
	s_xor_b64 s[26:27], exec, s[26:27]
	v_lshlrev_b64 v[106:107], 13, v[116:117]
	v_lshl_add_u64 v[106:107], s[24:25], 0, v[106:107]
	v_mov_b32_e32 v123, v1
	v_lshl_add_u64 v[106:107], v[106:107], 0, v[122:123]
	v_lshl_add_u64 v[106:107], v[106:107], 0, s[54:55]
	s_andn2_saveexec_b64 s[26:27], s[26:27]
	s_cbranch_execz .LBB0_1133
	v_mul_hi_i32 v106, v116, s94
	v_lshrrev_b32_e32 v107, 31, v106
	v_ashrrev_i32_e32 v106, 4, v106
	v_add_u32_e32 v107, v106, v107
	v_mul_lo_u32 v106, v107, s85
	v_sub_u32_e32 v106, v116, v106
	v_cmp_lt_i32_e64 s[38:39], 7, v106
	v_lshlrev_b32_e32 v108, 5, v106
	s_and_saveexec_b64 s[28:29], s[38:39]
	s_xor_b64 s[28:29], exec, s[28:29]
	v_lshlrev_b32_e32 v106, 11, v107
	v_add3_u32 v106, v108, v106, s95
	s_andn2_saveexec_b64 s[28:29], s[28:29]
	v_lshlrev_b32_e32 v106, 8, v107
	v_add3_u32 v106, v106, v108, s0
	s_or_b64 exec, exec, s[28:29]
	v_ashrrev_i32_e32 v107, 1, v127
	v_add_u32_e32 v108, v106, v107
	v_mov_b64_e32 v[106:107], s[4:5]
	v_mad_i64_i32 v[106:107], s[28:29], v108, s84, v[106:107]
	v_lshl_add_u64 v[106:107], s[22:23], 1, v[106:107]
	v_and_b32_e32 v108, 16, v122
	v_mov_b32_e32 v109, v1
	v_lshl_add_u64 v[106:107], v[106:107], 0, v[108:109]
	v_lshl_add_u64 v[106:107], v[106:107], 0, s[56:57]
.LBB0_1133:
	s_or_b64 exec, exec, s[26:27]
	global_load_dwordx4 v[106:109], v[106:107], off
	v_add_u32_e32 v110, 0x400, v110
	v_mul_hi_i32 v111, v110, s50
	v_lshrrev_b32_e32 v112, 31, v111
	v_ashrrev_i32_e32 v111, 4, v111
	v_add_u32_e32 v148, v111, v112
	v_mul_lo_u32 v111, v148, s48
	v_sub_u32_e32 v119, v110, v111
	v_add_u32_e32 v110, s31, v148
	v_lshlrev_b32_e32 v132, 3, v119
	v_cmp_gt_i32_e64 s[38:39], 64, v119
	v_cmp_lt_i32_e64 s[40:41], 63, v119
	v_ashrrev_i32_e32 v111, 31, v110
	v_lshlrev_b32_e32 v124, 4, v119
	v_and_b32_e32 v130, 8, v132
	s_and_saveexec_b64 s[26:27], s[40:41]
	s_xor_b64 s[26:27], exec, s[26:27]
	v_lshlrev_b64 v[134:135], 13, v[110:111]
	v_lshl_add_u64 v[110:111], s[24:25], 0, v[134:135]
	v_mov_b32_e32 v125, v1
	v_lshl_add_u64 v[110:111], v[110:111], 0, v[124:125]
	v_mov_b32_e32 v133, v1
	v_lshl_add_u64 v[112:113], v[110:111], 0, s[54:55]
	v_lshrrev_b32_e32 v125, 1, v119
	v_mov_b32_e32 v131, v1
	s_andn2_saveexec_b64 s[24:25], s[26:27]
	s_cbranch_execz .LBB0_1141
	v_mul_hi_i32 v112, v110, s94
	v_lshrrev_b32_e32 v113, 31, v112
	v_ashrrev_i32_e32 v112, 4, v112
	v_add_u32_e32 v113, v112, v113
	v_mul_lo_u32 v112, v113, s85
	v_sub_u32_e32 v112, v110, v112
	v_cmp_lt_i32_e64 s[40:41], 7, v112
	v_lshlrev_b32_e32 v121, 5, v112
	s_and_saveexec_b64 s[26:27], s[40:41]
	s_xor_b64 s[26:27], exec, s[26:27]
	v_lshlrev_b32_e32 v112, 11, v113
	v_add3_u32 v112, v121, v112, s95
	s_andn2_saveexec_b64 s[26:27], s[26:27]
	v_lshlrev_b32_e32 v112, 8, v113
	v_add3_u32 v112, v112, v121, s0
	s_or_b64 exec, exec, s[26:27]
	v_ashrrev_i32_e32 v125, 1, v119
	v_add_u32_e32 v119, v112, v125
	v_mov_b64_e32 v[112:113], s[4:5]
	v_mad_i64_i32 v[112:113], s[26:27], v119, s84, v[112:113]
	v_lshl_add_u64 v[112:113], s[22:23], 1, v[112:113]
	v_lshlrev_b32_e32 v128, 1, v130
	v_mov_b32_e32 v129, v1
	v_lshl_add_u64 v[112:113], v[112:113], 0, v[128:129]
	v_mov_b32_e32 v131, v1
	v_lshl_add_u64 v[112:113], v[112:113], 0, s[56:57]
	v_mov_b32_e32 v133, v1
	v_lshlrev_b64 v[134:135], 13, v[110:111]
.LBB0_1141:
	s_or_b64 exec, exec, s[24:25]
	global_load_dwordx4 v[110:113], v[112:113], off
	s_lshl_b64 s[22:23], s[22:23], 1
	v_mul_u32_u24_e32 v119, 0x610, v118
	s_add_u32 s24, s7, s22
	v_add3_u32 v123, 0, v119, v0
	s_addc_u32 s25, s18, s23
	v_lshlrev_b32_e32 v0, 1, v118
	v_lshlrev_b64 v[116:117], 13, v[116:117]
	v_lshlrev_b64 v[114:115], 13, v[114:115]
	v_lshl_add_u64 v[118:119], s[24:25], 0, v[0:1]
	v_lshlrev_b32_e32 v0, 3, v126
	v_lshlrev_b32_e32 v156, 3, v127
	v_mov_b32_e32 v157, v1
	s_add_u32 s22, s4, s22
	v_lshl_add_u64 v[134:135], v[134:135], 0, s[20:21]
	v_lshl_add_u64 v[116:117], v[116:117], 0, s[20:21]
	v_lshl_add_u64 v[114:115], v[114:115], 0, s[20:21]
	v_lshlrev_b32_e32 v121, 2, v136
	v_ashrrev_i32_e32 v141, 1, v126
	v_ashrrev_i32_e32 v142, 1, v127
	s_addc_u32 s23, s5, s23
	v_and_b32_e32 v126, 16, v120
	v_mov_b32_e32 v127, v1
	v_and_b32_e32 v128, 16, v122
	v_mov_b32_e32 v129, v1
	s_add_i32 s24, s31, 3
	s_mulk_i32 s33, 0x1200
	s_add_i32 s25, s31, 2
	s_add_i32 s26, s31, 1
	v_lshl_add_u64 v[132:133], v[132:133], 1, v[134:135]
	v_lshl_add_u64 v[116:117], v[156:157], 1, v[116:117]
	v_lshl_add_u64 v[114:115], v[0:1], 1, v[114:115]
	v_mul_lo_u32 v140, v137, s51
	v_mul_lo_u32 v139, v149, s51
	v_mul_lo_u32 v138, v148, s51
	v_lshl_add_u64 v[126:127], s[22:23], 0, v[126:127]
	v_lshl_add_u64 v[128:129], s[22:23], 0, v[128:129]
	v_lshl_add_u64 v[130:131], v[130:131], 1, s[22:23]
	v_add_u32_e32 v143, s31, v121
	v_add_u32_e32 v144, s24, v121
	v_lshl_or_b32 v145, v136, 7, s33
	v_add_u32_e32 v146, s25, v121
	v_add_u32_e32 v147, s26, v121
	v_add3_u32 v148, v148, s31, 16
	v_lshl_add_u64 v[132:133], s[44:45], 0, v[132:133]
	v_add3_u32 v149, v149, s31, 16
	v_lshl_add_u64 v[134:135], s[44:45], 0, v[116:117]
	v_add3_u32 v156, v137, s31, 16
	v_lshl_add_u64 v[136:137], s[44:45], 0, v[114:115]
	s_mov_b32 s27, 0
	s_mov_b32 s28, 0
	s_branch .LBB0_1144

; #define LAS __attribute__((address_space(3)))
; __device__ __forceinline__ bf16_t tobf(float f) { return (bf16_t)(cvt_pk_bf16(f, 0.f) & 0xffffu); }
; #define MFMA16(a, b, c) __builtin_amdgcn_mfma_f32_16x16x32_bf16((a), (b), (c), 0, 0, 0)
; #define S5_LOAD(rb_) do { _Pragma("unroll") for (int j_ = 0; j_ < 3; ++j_) { const int p_ = tid + j_ * 512, rr_ = p_ / 96, kc_ = p_ % 96, r_ = (rb_) * 16 + rr_; \
;         st[j_] = kc_ < 64 ? ld8(P + (size_t)(tokbase_of(r_) + (kc_ >> 1)) * INP + OFF_S5 + g * 16 + (kc_ & 1) * 8) : ld8(S5H + ((size_t)r_ * 16 + g) * 256 + (kc_ - 64) * 8); } } while (0)
; #define S5_STORE(buf_) do { _Pragma("unroll") for (int j_ = 0; j_ < 3; ++j_) { const int p_ = tid + j_ * 512, rr_ = p_ / 96, kc_ = p_ % 96; *(LAS u32x4*)(lds + (buf_) * BUF + rr_ * RST + kc_ * 16) = st[j_]; } } while (0)
; #define S5_LOAD(rb_) do { _Pragma("unroll") for (int j_ = 0; j_ < 2; ++j_) { const int p_ = tid + j_ * 512, rr_ = p_ >> 6, kc_ = p_ & 63, r_ = (rb_) * 16 + rr_; \
;         st[j_] = ld8(P + (size_t)(tokbase_of(r_) + (kc_ >> 1)) * INP + OFF_S5 + g * 16 + (kc_ & 1) * 8); } } while (0)
; #define S5_STORE(buf_) do { _Pragma("unroll") for (int j_ = 0; j_ < 2; ++j_) { const int p_ = tid + j_ * 512, rr_ = p_ >> 6, kc_ = p_ & 63; *(LAS u32x4*)(lds + (buf_) * BUF + rr_ * RST + kc_ * 16) = st[j_]; } } while (0)
; __device__ __forceinline__ void s5_pass2_block(LAS unsigned char* lds, int bt, int l, const bf16_t* P, const bf16_t* BM2, const bf16_t* S5H, bf16_t* YB) {
;     ...
;     for (int i = 0; i < 9; ++i) {
;         const int rb = rg * 9 + i;
;         S5_STORE(i & 1);
;         __syncthreads();
;         if (i < 8) S5_LOAD(rb + 1);
;         const LAS unsigned char* ab = lds + (i & 1) * BUF + fr * RST + fq * 16;
;         f32x4 acc = (f32x4){0.f, 0.f, 0.f, 0.f};
; #pragma unroll
;         for (int ks = 0; ks < 24; ++ks) acc = MFMA16(*(const LAS bf16x8*)(ab + ks * 64), bw[ks], acc);
; #pragma unroll
;         for (int q = 0; q < 4; ++q) YB[(size_t)(tokbase_of(rb * 16 + fq * 4 + q) + cb) * 256 + g * 16 + fr] = tobf(acc[q]);
;     }
.LBB0_1143:
	s_or_b64 exec, exec, s[20:21]
	v_add_u32_e32 v166, s29, v123
	ds_read_b128 v[114:117], v166
	ds_read_b128 v[162:165], v166 offset:64
	v_mul_hi_u32 v0, v144, s94
	v_lshrrev_b32_e32 v112, 4, v0
	v_mul_lo_u32 v0, v112, s9
	v_mul_lo_u32 v112, v112, s85
	v_sub_u32_e32 v157, s24, v112
	v_mul_hi_u32 v112, v146, s94
	v_lshrrev_b32_e32 v112, 4, v112
	s_waitcnt lgkmcnt(0)
	v_mfma_f32_16x16x32_bf16 v[114:117], v[114:117], v[98:101], 0
	v_mul_lo_u32 v113, v112, s9
	v_mul_lo_u32 v112, v112, s85
	v_sub_u32_e32 v159, s25, v112
	v_mfma_f32_16x16x32_bf16 v[114:117], v[162:165], v[94:97], v[114:117]
	ds_read_b128 v[162:165], v166 offset:128
	v_mul_hi_u32 v112, v147, s94
	v_lshrrev_b32_e32 v112, 4, v112
	s_movk_i32 s14, 0xf700
	v_mul_lo_u32 v160, v112, s14
	v_mul_lo_u32 v112, v112, s85
	v_sub_u32_e32 v158, 0x4040, v113
	v_sub_u32_e32 v161, s26, v112
	s_waitcnt lgkmcnt(0)
	v_mfma_f32_16x16x32_bf16 v[114:117], v[162:165], v[90:93], v[114:117]
	ds_read_b128 v[162:165], v166 offset:192
	global_load_dwordx4 v[110:113], v[110:111], off
	s_movk_i32 s14, 0x4020
	v_xor_b32_e32 v0, 0xffffff60, v0
	s_add_i32 s28, s28, 1
	v_add_u32_e32 v144, 16, v144
	v_add_u32_e32 v146, 16, v146
	s_waitcnt lgkmcnt(0)
	v_mfma_f32_16x16x32_bf16 v[114:117], v[162:165], v[86:89], v[114:117]
	ds_read_b128 v[162:165], v166 offset:256
	v_add_u32_e32 v147, 16, v147
	v_lshl_add_u64 v[132:133], v[132:133], 0, s[16:17]
	v_lshl_add_u64 v[134:135], v[134:135], 0, s[16:17]
	v_lshl_add_u64 v[136:137], v[136:137], 0, s[16:17]
	s_waitcnt lgkmcnt(0)
	v_mfma_f32_16x16x32_bf16 v[114:117], v[162:165], v[82:85], v[114:117]
	ds_read_b128 v[162:165], v166 offset:320
	s_waitcnt lgkmcnt(0)
	v_mfma_f32_16x16x32_bf16 v[114:117], v[162:165], v[78:81], v[114:117]
	ds_read_b128 v[162:165], v166 offset:384
	s_waitcnt lgkmcnt(0)
	v_mfma_f32_16x16x32_bf16 v[114:117], v[162:165], v[74:77], v[114:117]
	ds_read_b128 v[162:165], v166 offset:448
	s_waitcnt lgkmcnt(0)
	v_mfma_f32_16x16x32_bf16 v[114:117], v[162:165], v[70:73], v[114:117]
	ds_read_b128 v[162:165], v166 offset:512
	s_waitcnt lgkmcnt(0)
	v_mfma_f32_16x16x32_bf16 v[114:117], v[162:165], v[66:69], v[114:117]
	ds_read_b128 v[162:165], v166 offset:576
	s_waitcnt lgkmcnt(0)
	v_mfma_f32_16x16x32_bf16 v[114:117], v[162:165], v[62:65], v[114:117]
	ds_read_b128 v[162:165], v166 offset:640
	s_waitcnt lgkmcnt(0)
	v_mfma_f32_16x16x32_bf16 v[114:117], v[162:165], v[58:61], v[114:117]
	ds_read_b128 v[162:165], v166 offset:704
	s_waitcnt lgkmcnt(0)
	v_mfma_f32_16x16x32_bf16 v[114:117], v[162:165], v[54:57], v[114:117]
	ds_read_b128 v[162:165], v166 offset:768
	s_waitcnt lgkmcnt(0)
	v_mfma_f32_16x16x32_bf16 v[114:117], v[162:165], v[50:53], v[114:117]
	ds_read_b128 v[162:165], v166 offset:832
	s_waitcnt lgkmcnt(0)
	v_mfma_f32_16x16x32_bf16 v[114:117], v[162:165], v[46:49], v[114:117]
	ds_read_b128 v[162:165], v166 offset:896
	s_waitcnt lgkmcnt(0)
	v_mfma_f32_16x16x32_bf16 v[114:117], v[162:165], v[42:45], v[114:117]
	ds_read_b128 v[162:165], v166 offset:960
	s_waitcnt lgkmcnt(0)
	v_mfma_f32_16x16x32_bf16 v[114:117], v[162:165], v[38:41], v[114:117]
	ds_read_b128 v[162:165], v166 offset:1024
	s_waitcnt lgkmcnt(0)
	v_mfma_f32_16x16x32_bf16 v[114:117], v[162:165], v[34:37], v[114:117]
	ds_read_b128 v[162:165], v166 offset:1088
	s_waitcnt lgkmcnt(0)
	v_mfma_f32_16x16x32_bf16 v[114:117], v[162:165], v[30:33], v[114:117]
	ds_read_b128 v[162:165], v166 offset:1152
	s_waitcnt lgkmcnt(0)
	v_mfma_f32_16x16x32_bf16 v[114:117], v[162:165], v[26:29], v[114:117]
	ds_read_b128 v[162:165], v166 offset:1216
	s_waitcnt lgkmcnt(0)
	v_mfma_f32_16x16x32_bf16 v[114:117], v[162:165], v[22:25], v[114:117]
	ds_read_b128 v[162:165], v166 offset:1280
	s_waitcnt lgkmcnt(0)
	v_mfma_f32_16x16x32_bf16 v[114:117], v[162:165], v[18:21], v[114:117]
	ds_read_b128 v[162:165], v166 offset:1344
	s_waitcnt lgkmcnt(0)
	v_mfma_f32_16x16x32_bf16 v[114:117], v[162:165], v[14:17], v[114:117]
	ds_read_b128 v[162:165], v166 offset:1408
	s_waitcnt lgkmcnt(0)
	v_mfma_f32_16x16x32_bf16 v[114:117], v[162:165], v[6:9], v[114:117]
	ds_read_b128 v[162:165], v166 offset:1472
	s_waitcnt lgkmcnt(0)
	v_mfma_f32_16x16x32_bf16 v[114:117], v[162:165], v[2:5], v[114:117]
	v_add_u32_e32 v162, s27, v143
	v_mul_hi_u32 v163, v162, s94
	v_lshrrev_b32_e32 v163, 4, v163
	v_lshlrev_b32_e32 v164, 11, v163
	v_lshlrev_b32_e32 v165, 8, v163
	v_mul_lo_u32 v163, v163, s85
	v_sub_u32_e32 v162, v162, v163
	v_cmp_gt_u32_e64 s[40:41], 8, v162
	v_lshlrev_b32_e32 v162, 5, v162
	v_add3_u32 v163, v165, v162, s0
	v_add3_u32 v162, v164, v162, s95
	v_cndmask_b32_e64 v162, v162, v163, s[40:41]
	v_add_u32_e32 v162, s30, v162
	v_ashrrev_i32_e32 v163, 31, v162
	v_lshlrev_b64 v[162:163], 9, v[162:163]
	v_lshl_add_u64 v[162:163], v[118:119], 0, v[162:163]
	v_cvt_pk_bf16_f32 v114, v114, v1
	global_store_short v[162:163], v114, off
	v_add_u32_e32 v163, s27, v121
	v_add_u32_e32 v114, v163, v161
	v_add_u32_e32 v161, v145, v165
	v_cmp_gt_u32_e64 s[40:41], 8, v114
	v_add3_u32 v114, v161, v160, s14
	v_add_u32_e32 v164, v145, v164
	s_movk_i32 s14, 0xff20
	v_cvt_pk_bf16_f32 v162, v115, v1
	v_add3_u32 v115, v164, v160, s14
	v_cndmask_b32_e64 v114, v115, v114, s[40:41]
	v_add_u32_e32 v114, s30, v114
	v_ashrrev_i32_e32 v115, 31, v114
	v_lshlrev_b64 v[114:115], 9, v[114:115]
	v_lshl_add_u64 v[114:115], v[118:119], 0, v[114:115]
	global_store_short v[114:115], v162, off
	v_add_u32_e32 v114, v163, v159
	s_movk_i32 s14, 0xbf00
	v_cmp_gt_u32_e64 s[40:41], 8, v114
	v_add_u32_e32 v114, v161, v158
	v_add3_u32 v115, v164, v158, s14
	v_cndmask_b32_e64 v114, v115, v114, s[40:41]
	v_add_u32_e32 v114, s30, v114
	v_ashrrev_i32_e32 v115, 31, v114
	v_lshlrev_b64 v[114:115], 9, v[114:115]
	v_lshl_add_u64 v[114:115], v[118:119], 0, v[114:115]
	v_cvt_pk_bf16_f32 v116, v116, v1
	global_store_short v[114:115], v116, off
	v_add_u32_e32 v114, v163, v157
	s_movk_i32 s14, 0x4100
	v_cmp_gt_u32_e64 s[40:41], 8, v114
	v_add3_u32 v114, v161, v0, s14
	v_add_u32_e32 v0, v164, v0
	v_cndmask_b32_e64 v0, v0, v114, s[40:41]
	v_add_u32_e32 v114, s30, v0
	v_ashrrev_i32_e32 v115, 31, v114
	v_lshlrev_b64 v[114:115], 9, v[114:115]
	s_add_i32 s27, s27, 16
	v_lshl_add_u64 v[114:115], v[118:119], 0, v[114:115]
	v_add_u32_e32 v145, 0x200, v145
	s_cmpk_lg_i32 s27, 0x80
	v_cvt_pk_bf16_f32 v116, v117, v1
	global_store_short v[114:115], v116, off
	s_cbranch_scc0 .LBB0_1116

; #define S5_LOAD(rb_) do { _Pragma("unroll") for (int j_ = 0; j_ < 3; ++j_) { const int p_ = tid + j_ * 512, rr_ = p_ / 96, kc_ = p_ % 96, r_ = (rb_) * 16 + rr_; \
;         st[j_] = kc_ < 64 ? ld8(P + (size_t)(tokbase_of(r_) + (kc_ >> 1)) * INP + OFF_S5 + g * 16 + (kc_ & 1) * 8) : ld8(S5H + ((size_t)r_ * 16 + g) * 256 + (kc_ - 64) * 8); } } while (0)
; #define S5_STORE(buf_) do { _Pragma("unroll") for (int j_ = 0; j_ < 3; ++j_) { const int p_ = tid + j_ * 512, rr_ = p_ / 96, kc_ = p_ % 96; *(LAS u32x4*)(lds + (buf_) * BUF + rr_ * RST + kc_ * 16) = st[j_]; } } while (0)
; #define S5_LOAD(rb_) do { _Pragma("unroll") for (int j_ = 0; j_ < 2; ++j_) { const int p_ = tid + j_ * 512, rr_ = p_ >> 6, kc_ = p_ & 63, r_ = (rb_) * 16 + rr_; \
;         st[j_] = ld8(P + (size_t)(tokbase_of(r_) + (kc_ >> 1)) * INP + OFF_S5 + g * 16 + (kc_ & 1) * 8); } } while (0)
; #define S5_STORE(buf_) do { _Pragma("unroll") for (int j_ = 0; j_ < 2; ++j_) { const int p_ = tid + j_ * 512, rr_ = p_ >> 6, kc_ = p_ & 63; *(LAS u32x4*)(lds + (buf_) * BUF + rr_ * RST + kc_ * 16) = st[j_]; } } while (0)
; __device__ __forceinline__ void s5_pass2_block(LAS unsigned char* lds, int bt, int l, const bf16_t* P, const bf16_t* BM2, const bf16_t* S5H, bf16_t* YB) {
;     ...
;     __syncthreads();
;     S5_LOAD(rg * 9);
;     for (int i = 0; i < 9; ++i) {
;         const int rb = rg * 9 + i;
;         S5_STORE(i & 1);
;         __syncthreads();
;         if (i < 8) S5_LOAD(rb + 1);
.LBB0_1150:
	s_or_b64 exec, exec, s[20:21]
	global_load_dwordx4 v[102:105], v[102:103], off
	v_mov_b64_e32 v[106:107], v[134:135]
	s_and_saveexec_b64 s[20:21], s[36:37]
	s_cbranch_execz .LBB0_1156
	v_add_u32_e32 v0, s27, v149
	v_mul_hi_i32 v106, v0, s94
	v_lshrrev_b32_e32 v107, 31, v106
	v_ashrrev_i32_e32 v106, 4, v106
	v_add_u32_e32 v106, v106, v107
	v_mul_lo_u32 v107, v106, s85
	v_sub_u32_e32 v0, v0, v107
	v_cmp_lt_i32_e64 s[40:41], 7, v0
	v_lshlrev_b32_e32 v107, 5, v0
	s_and_saveexec_b64 s[22:23], s[40:41]
	s_xor_b64 s[22:23], exec, s[22:23]
	v_lshlrev_b32_e32 v0, 11, v106
	v_add3_u32 v0, v107, v0, s95
	s_andn2_saveexec_b64 s[22:23], s[22:23]
	v_lshlrev_b32_e32 v0, 8, v106
	v_add3_u32 v0, v0, v107, s0
	s_or_b64 exec, exec, s[22:23]
	v_add_u32_e32 v0, v0, v142
	v_mad_i64_i32 v[106:107], s[22:23], v0, s84, v[128:129]
	v_lshl_add_u64 v[106:107], v[106:107], 0, s[56:57]
.LBB0_1156:
	s_or_b64 exec, exec, s[20:21]
	global_load_dwordx4 v[106:109], v[106:107], off
	v_mov_b64_e32 v[110:111], v[132:133]
	s_and_saveexec_b64 s[20:21], s[38:39]
	s_cbranch_execz .LBB0_1143
	v_add_u32_e32 v0, s27, v148
	v_mul_hi_i32 v110, v0, s94
	v_lshrrev_b32_e32 v111, 31, v110
	v_ashrrev_i32_e32 v110, 4, v110
	v_add_u32_e32 v110, v110, v111
	v_mul_lo_u32 v111, v110, s85
	v_sub_u32_e32 v0, v0, v111
	v_cmp_lt_i32_e64 s[40:41], 7, v0
	v_lshlrev_b32_e32 v111, 5, v0
	s_and_saveexec_b64 s[22:23], s[40:41]
	s_xor_b64 s[22:23], exec, s[22:23]
	v_lshlrev_b32_e32 v0, 11, v110
	v_add3_u32 v0, v111, v0, s95
	s_andn2_saveexec_b64 s[22:23], s[22:23]
	s_cbranch_execz .LBB0_1142
	v_lshlrev_b32_e32 v0, 8, v110
	v_add3_u32 v0, v0, v111, s0
	s_branch .LBB0_1142

; __device__ __forceinline__ float bf1(bf16_t v) { return __uint_as_float(((unsigned)v) << 16); }
; __device__ __forceinline__ bf16_t tobf(float f) { return (bf16_t)(cvt_pk_bf16(f, 0.f) & 0xffffu); }
; __device__ __forceinline__ float siluf(float x) { return x * __builtin_amdgcn_rcpf(1.f + __expf(-x)); }
; template <bool PASS2> ...
;     ...
;     if (PASS2) {
; #pragma unroll
;         for (int tb = 0; tb < 2; ++tb)
; #pragma unroll
;             for (int cb = 0; cb < 4; ++cb)
; #pragma unroll
;                 for (int q = 0; q < 4; ++q) xl[(tb * 16 + fq * 4 + q) * 68 + cb * 16 + fr] = yacc[tb][cb][q];
;         asm volatile("s_waitcnt lgkmcnt(0)" ::: "memory");
;         { bf16_t gpv[32];
; #pragma unroll
;         for (int s = 0; s < 32; ++s) gpv[s] = P[(size_t)(rbase + t0 + s) * INP + OFF_GATE + 2 * 256 + blk * 64 + lane];
; #pragma unroll
;         for (int s = 0; s < 32; ++s) Z2[(size_t)(rbase + t0 + s) * 256 + blk * 64 + lane] = tobf(xl[s * 68 + lane] * siluf(bf1(gpv[s]))); }
.LBB0_1163:
	s_add_i32 s24, s24, s96
	s_ashr_i32 s25, s24, 31
	s_mul_i32 s15, s24, 0x2200
	s_mul_hi_i32 s14, s24, 0x2200
	s_add_u32 s15, s1, s15
	s_addc_u32 s14, s33, s14
	s_lshl_b32 s88, s19, 1
	s_add_u32 s20, s15, s88
	s_addc_u32 s21, s14, 0
	s_or_b32 s26, s24, 1
	s_ashr_i32 s27, s26, 31
	s_mul_i32 s15, s26, 0x2200
	v_add_u32_e32 v0, 0x1000, v91
	v_add_u32_e32 v9, 0x1400, v91
	s_mul_hi_i32 s14, s26, 0x2200
	s_add_u32 s15, s1, s15
	ds_write2_b32 v91, v18, v24 offset1:16
	ds_write2_b32 v91, v19, v25 offset0:68 offset1:84
	ds_write2_b32 v91, v22, v26 offset0:136 offset1:152
	ds_write2_b32 v91, v23, v27 offset0:204 offset1:220
	ds_write2_b32 v91, v28, v36 offset0:32 offset1:48
	ds_write2_b32 v91, v29, v37 offset0:100 offset1:116
	ds_write2_b32 v91, v30, v38 offset0:168 offset1:184
	ds_write2_b32 v91, v31, v39 offset0:236 offset1:252
	ds_write2_b32 v0, v34, v46 offset0:64 offset1:80
	ds_write2_b32 v0, v35, v47 offset0:132 offset1:148
	ds_write2_b32 v0, v32, v40 offset0:200 offset1:216
	ds_write2_b32 v9, v33, v41 offset0:12 offset1:28
	ds_write2_b32 v0, v42, v48 offset0:96 offset1:112
	ds_write2_b32 v0, v43, v49 offset0:164 offset1:180
	ds_write2_b32 v0, v44, v50 offset0:232 offset1:248
	ds_write2_b32 v9, v45, v51 offset0:44 offset1:60
	v_mov_b32_e32 v9, v1
	s_addc_u32 s14, s33, s14
	v_lshl_add_u64 v[26:27], s[20:21], 0, v[8:9]
	s_add_u32 s20, s15, s88
	s_addc_u32 s21, s14, 0
	v_lshl_add_u64 v[20:21], s[20:21], 0, v[8:9]
	s_or_b32 s20, s24, 2
	s_ashr_i32 s21, s20, 31
	s_mul_i32 s15, s20, 0x2200
	s_mul_hi_i32 s14, s20, 0x2200
	s_add_u32 s15, s1, s15
	s_addc_u32 s14, s33, s14
	s_add_u32 s22, s15, s88
	s_addc_u32 s23, s14, 0
	s_or_b32 s34, s24, 3
	s_ashr_i32 s35, s34, 31
	s_mul_i32 s15, s34, 0x2200
	s_mul_hi_i32 s14, s34, 0x2200
	s_add_u32 s15, s1, s15
	s_addc_u32 s14, s33, s14
	v_lshl_add_u64 v[14:15], s[22:23], 0, v[8:9]
	s_add_u32 s22, s15, s88
	s_addc_u32 s23, s14, 0
	s_or_b32 s28, s24, 4
	s_ashr_i32 s29, s28, 31
	s_mul_i32 s15, s28, 0x2200
	s_mul_hi_i32 s14, s28, 0x2200
	s_add_u32 s15, s1, s15
	s_addc_u32 s14, s33, s14
	v_lshl_add_u64 v[16:17], s[22:23], 0, v[8:9]
	s_add_u32 s22, s15, s88
	s_addc_u32 s23, s14, 0
	s_or_b32 vcc_lo, s24, 5
	s_ashr_i32 vcc_hi, vcc_lo, 31
	s_mul_i32 s15, vcc_lo, 0x2200
	s_mul_hi_i32 s14, vcc_lo, 0x2200
	s_add_u32 s15, s1, s15
	s_addc_u32 s14, s33, s14
	v_lshl_add_u64 v[18:19], s[22:23], 0, v[8:9]
	s_add_u32 s22, s15, s88
	s_addc_u32 s23, s14, 0
	s_or_b32 s80, s24, 6
	s_ashr_i32 s81, s80, 31
	s_mul_i32 s15, s80, 0x2200
	s_mul_hi_i32 s14, s80, 0x2200
	s_add_u32 s15, s1, s15
	s_addc_u32 s14, s33, s14
	v_lshl_add_u64 v[22:23], s[22:23], 0, v[8:9]
	s_add_u32 s22, s15, s88
	s_addc_u32 s23, s14, 0
	s_or_b32 s78, s24, 7
	s_ashr_i32 s79, s78, 31
	s_mul_i32 s15, s78, 0x2200
	s_mul_hi_i32 s14, s78, 0x2200
	s_add_u32 s15, s1, s15
	s_addc_u32 s14, s33, s14
	v_lshl_add_u64 v[24:25], s[22:23], 0, v[8:9]
	s_add_u32 s22, s15, s88
	s_addc_u32 s23, s14, 0
	s_or_b32 s74, s24, 8
	s_ashr_i32 s75, s74, 31
	s_mul_i32 s15, s74, 0x2200
	s_mul_hi_i32 s14, s74, 0x2200
	s_add_u32 s15, s1, s15
	s_addc_u32 s14, s33, s14
	v_lshl_add_u64 v[30:31], s[22:23], 0, v[8:9]
	s_add_u32 s22, s15, s88
	s_addc_u32 s23, s14, 0
	s_or_b32 s68, s24, 9
	s_ashr_i32 s69, s68, 31
	s_mul_i32 s15, s68, 0x2200
	s_mul_hi_i32 s14, s68, 0x2200
	s_add_u32 s15, s1, s15
	s_addc_u32 s14, s33, s14
	v_lshl_add_u64 v[28:29], s[22:23], 0, v[8:9]
	s_add_u32 s22, s15, s88
	s_addc_u32 s23, s14, 0
	s_or_b32 s66, s24, 10
	s_ashr_i32 s67, s66, 31
	s_mul_i32 s15, s66, 0x2200
	s_mul_hi_i32 s14, s66, 0x2200
	s_add_u32 s15, s1, s15
	s_addc_u32 s14, s33, s14
	v_lshl_add_u64 v[32:33], s[22:23], 0, v[8:9]
	s_add_u32 s22, s15, s88
	s_addc_u32 s23, s14, 0
	s_or_b32 s62, s24, 11
	s_ashr_i32 s63, s62, 31
	s_mul_i32 s15, s62, 0x2200
	s_mul_hi_i32 s14, s62, 0x2200
	s_add_u32 s15, s1, s15
	s_addc_u32 s14, s33, s14
	v_lshl_add_u64 v[34:35], s[22:23], 0, v[8:9]
	s_add_u32 s22, s15, s88
	s_addc_u32 s23, s14, 0
	s_or_b32 s58, s24, 12
	s_ashr_i32 s59, s58, 31
	s_mul_i32 s15, s58, 0x2200
	s_mul_hi_i32 s14, s58, 0x2200
	s_add_u32 s15, s1, s15
	s_addc_u32 s14, s33, s14
	v_lshl_add_u64 v[36:37], s[22:23], 0, v[8:9]
	s_add_u32 s22, s15, s88
	s_addc_u32 s23, s14, 0
	s_or_b32 s56, s24, 13
	s_ashr_i32 s57, s56, 31
	s_mul_i32 s15, s56, 0x2200
	s_mul_hi_i32 s14, s56, 0x2200
	s_add_u32 s15, s1, s15
	s_waitcnt lgkmcnt(0)
; __device__ __forceinline__ float bf1(bf16_t v) { return __uint_as_float(((unsigned)v) << 16); }
; __device__ __forceinline__ bf16_t tobf(float f) { return (bf16_t)(cvt_pk_bf16(f, 0.f) & 0xffffu); }
; __device__ __forceinline__ float siluf(float x) { return x * __builtin_amdgcn_rcpf(1.f + __expf(-x)); }
; template <bool PASS2> ...
;     ...
;         { bf16_t gpv[32];
; #pragma unroll
;         for (int s = 0; s < 32; ++s) gpv[s] = P[(size_t)(rbase + t0 + s) * INP + OFF_GATE + 2 * 256 + blk * 64 + lane];
; #pragma unroll
;         for (int s = 0; s < 32; ++s) Z2[(size_t)(rbase + t0 + s) * 256 + blk * 64 + lane] = tobf(xl[s * 68 + lane] * siluf(bf1(gpv[s]))); }
	s_addc_u32 s14, s33, s14
	v_lshl_add_u64 v[38:39], s[22:23], 0, v[8:9]
	s_add_u32 s22, s15, s88
	global_load_ushort v0, v[26:27], off offset:3392
	global_load_ushort v70, v[20:21], off offset:3392
	global_load_ushort v71, v[14:15], off offset:3392
	global_load_ushort v72, v[16:17], off offset:3392
	global_load_ushort v73, v[18:19], off offset:3392
	s_addc_u32 s23, s14, 0
	s_or_b32 s54, s24, 14
	s_ashr_i32 s55, s54, 31
	s_mul_i32 s15, s54, 0x2200
	s_mul_hi_i32 s14, s54, 0x2200
	s_add_u32 s15, s1, s15
	s_addc_u32 s14, s33, s14
	v_lshl_add_u64 v[40:41], s[22:23], 0, v[8:9]
	s_add_u32 s22, s15, s88
	s_addc_u32 s23, s14, 0
	s_or_b32 s52, s24, 15
	s_ashr_i32 s53, s52, 31
	s_mul_i32 s15, s52, 0x2200
	s_mul_hi_i32 s14, s52, 0x2200
	s_add_u32 s15, s1, s15
	s_addc_u32 s14, s33, s14
	v_lshl_add_u64 v[42:43], s[22:23], 0, v[8:9]
	s_add_u32 s22, s15, s88
	s_addc_u32 s23, s14, 0
	s_or_b32 s50, s24, 16
	s_ashr_i32 s51, s50, 31
	s_mul_i32 s15, s50, 0x2200
	s_mul_hi_i32 s14, s50, 0x2200
	s_add_u32 s15, s1, s15
	s_addc_u32 s14, s33, s14
	v_lshl_add_u64 v[44:45], s[22:23], 0, v[8:9]
	s_add_u32 s22, s15, s88
	s_addc_u32 s23, s14, 0
	s_or_b32 s48, s24, 17
	s_ashr_i32 s49, s48, 31
	s_mul_i32 s15, s48, 0x2200
	s_mul_hi_i32 s14, s48, 0x2200
	s_add_u32 s15, s1, s15
	s_addc_u32 s14, s33, s14
	v_lshl_add_u64 v[46:47], s[22:23], 0, v[8:9]
	s_add_u32 s22, s15, s88
	s_addc_u32 s23, s14, 0
	s_or_b32 s46, s24, 18
	s_ashr_i32 s47, s46, 31
	s_mul_i32 s15, s46, 0x2200
	s_mul_hi_i32 s14, s46, 0x2200
	s_add_u32 s15, s1, s15
	s_addc_u32 s14, s33, s14
	v_lshl_add_u64 v[48:49], s[22:23], 0, v[8:9]
	s_add_u32 s22, s15, s88
	s_addc_u32 s23, s14, 0
	s_or_b32 s44, s24, 19
	s_ashr_i32 s45, s44, 31
	s_mul_i32 s15, s44, 0x2200
	s_mul_hi_i32 s14, s44, 0x2200
	s_add_u32 s15, s1, s15
	s_addc_u32 s14, s33, s14
	v_lshl_add_u64 v[50:51], s[22:23], 0, v[8:9]
	s_add_u32 s22, s15, s88
	s_addc_u32 s23, s14, 0
	s_or_b32 s42, s24, 20
	s_ashr_i32 s43, s42, 31
	s_mul_i32 s15, s42, 0x2200
	s_mul_hi_i32 s14, s42, 0x2200
	s_add_u32 s15, s1, s15
	s_addc_u32 s14, s33, s14
	v_lshl_add_u64 v[52:53], s[22:23], 0, v[8:9]
	s_add_u32 s22, s15, s88
	s_addc_u32 s23, s14, 0
	s_or_b32 s40, s24, 21
	s_ashr_i32 s41, s40, 31
	s_mul_i32 s15, s40, 0x2200
	s_mul_hi_i32 s14, s40, 0x2200
	s_add_u32 s15, s1, s15
	s_addc_u32 s14, s33, s14
	v_lshl_add_u64 v[54:55], s[22:23], 0, v[8:9]
	s_add_u32 s22, s15, s88
	s_addc_u32 s23, s14, 0
	s_or_b32 s38, s24, 22
	s_ashr_i32 s39, s38, 31
	s_mul_i32 s15, s38, 0x2200
	s_mul_hi_i32 s14, s38, 0x2200
	s_add_u32 s15, s1, s15
	s_addc_u32 s14, s33, s14
	v_lshl_add_u64 v[56:57], s[22:23], 0, v[8:9]
	s_add_u32 s22, s15, s88
	s_addc_u32 s23, s14, 0
	s_or_b32 s36, s24, 23
	s_ashr_i32 s37, s36, 31
	s_mul_i32 s15, s36, 0x2200
	s_mul_hi_i32 s14, s36, 0x2200
	s_add_u32 s15, s1, s15
	s_addc_u32 s14, s33, s14
	v_lshl_add_u64 v[58:59], s[22:23], 0, v[8:9]
	s_add_u32 s22, s15, s88
	s_addc_u32 s23, s14, 0
	v_lshl_add_u64 v[26:27], s[22:23], 0, v[8:9]
	s_or_b32 s22, s24, 24
	s_ashr_i32 s23, s22, 31
	s_mul_i32 s15, s22, 0x2200
	global_load_ushort v22, v[22:23], off offset:3392
	s_nop 0
	global_load_ushort v23, v[24:25], off offset:3392
	s_nop 0
	global_load_ushort v24, v[30:31], off offset:3392
	s_mul_hi_i32 s14, s22, 0x2200
	s_add_u32 s15, s1, s15
	s_addc_u32 s14, s33, s14
	s_add_u32 s30, s15, s88
	s_addc_u32 s31, s14, 0
	v_lshl_add_u64 v[60:61], s[30:31], 0, v[8:9]
	s_or_b32 s30, s24, 25
	s_ashr_i32 s31, s30, 31
	s_mul_i32 s15, s30, 0x2200
	s_mul_hi_i32 s14, s30, 0x2200
	s_add_u32 s15, s1, s15
	s_addc_u32 s14, s33, s14
	s_add_u32 s60, s15, s88
	s_addc_u32 s61, s14, 0
	s_or_b32 s96, s24, 26
	s_ashr_i32 s97, s96, 31
	s_mul_i32 s15, s96, 0x2200
	s_mul_hi_i32 s14, s96, 0x2200
	s_add_u32 s15, s1, s15
	s_addc_u32 s14, s33, s14
	v_lshl_add_u64 v[62:63], s[60:61], 0, v[8:9]
	s_add_u32 s60, s15, s88
	s_addc_u32 s61, s14, 0
	s_or_b32 s82, s24, 27
	s_ashr_i32 s83, s82, 31
	s_mul_i32 s15, s82, 0x2200
	s_mul_hi_i32 s14, s82, 0x2200
	s_add_u32 s15, s1, s15
	s_addc_u32 s14, s33, s14
	v_lshl_add_u64 v[20:21], s[60:61], 0, v[8:9]
	s_add_u32 s60, s15, s88
	s_addc_u32 s61, s14, 0
	s_or_b32 s76, s24, 28
	s_ashr_i32 s77, s76, 31
	s_mul_i32 s15, s76, 0x2200
	s_mul_hi_i32 s14, s76, 0x2200
	s_add_u32 s15, s1, s15
	s_addc_u32 s14, s33, s14
	v_lshl_add_u64 v[64:65], s[60:61], 0, v[8:9]
	s_add_u32 s60, s15, s88
	s_addc_u32 s61, s14, 0
	s_or_b32 s72, s24, 29
	s_ashr_i32 s73, s72, 31
	s_mul_i32 s15, s72, 0x2200
	s_mul_hi_i32 s14, s72, 0x2200
	s_add_u32 s15, s1, s15
	s_waitcnt vmcnt(0) lgkmcnt(0)
	v_lshlrev_b32_e32 v0, 16, v0
	s_addc_u32 s14, s33, s14
	v_mul_f32_e32 v14, 0xbfb8aa3b, v0
	v_lshl_add_u64 v[66:67], s[60:61], 0, v[8:9]
	s_add_u32 s60, s15, s88
	v_exp_f32_e32 v14, v14
	s_addc_u32 s61, s14, 0
	v_lshl_add_u64 v[16:17], s[60:61], 0, v[8:9]
	s_or_b32 s60, s24, 30
	s_ashr_i32 s61, s60, 31
	s_mul_i32 s15, s60, 0x2200
	s_mul_hi_i32 s14, s60, 0x2200
	s_add_u32 s15, s1, s15
	v_add_f32_e32 v14, 1.0, v14
	s_addc_u32 s14, s33, s14
	ds_read_b32 v25, v90
	v_rcp_f32_e32 v30, v14
	s_add_u32 s64, s15, s88
	s_addc_u32 s65, s14, 0
	v_lshl_add_u64 v[68:69], s[64:65], 0, v[8:9]
	s_or_b32 s64, s24, 31
	s_ashr_i32 s65, s64, 31
	s_mul_i32 s15, s64, 0x2200
	v_mul_f32_e32 v0, v30, v0
	global_load_ushort v28, v[28:29], off offset:3392
	s_nop 0
	global_load_ushort v29, v[32:33], off offset:3392
	global_load_ushort v30, v[34:35], off offset:3392
	global_load_ushort v31, v[36:37], off offset:3392
	s_nop 0
	global_load_ushort v32, v[38:39], off offset:3392
	global_load_ushort v33, v[40:41], off offset:3392
	global_load_ushort v34, v[42:43], off offset:3392
	global_load_ushort v35, v[44:45], off offset:3392
	global_load_ushort v36, v[46:47], off offset:3392
	global_load_ushort v37, v[48:49], off offset:3392
	global_load_ushort v38, v[50:51], off offset:3392
	global_load_ushort v39, v[52:53], off offset:3392
	global_load_ushort v40, v[54:55], off offset:3392
	global_load_ushort v41, v[56:57], off offset:3392
	global_load_ushort v42, v[58:59], off offset:3392
	s_nop 0
	global_load_ushort v26, v[26:27], off offset:3392
	v_lshlrev_b32_e32 v27, 16, v70
	s_mul_hi_i32 s14, s64, 0x2200
	s_add_u32 s15, s1, s15
	s_waitcnt lgkmcnt(0)
; __device__ __forceinline__ float bf1(bf16_t v) { return __uint_as_float(((unsigned)v) << 16); }
; __device__ __forceinline__ bf16_t tobf(float f) { return (bf16_t)(cvt_pk_bf16(f, 0.f) & 0xffffu); }
; __device__ __forceinline__ float siluf(float x) { return x * __builtin_amdgcn_rcpf(1.f + __expf(-x)); }
; template <bool PASS2> ...
;     ...
;         { bf16_t gpv[32];
; #pragma unroll
;         for (int s = 0; s < 32; ++s) gpv[s] = P[(size_t)(rbase + t0 + s) * INP + OFF_GATE + 2 * 256 + blk * 64 + lane];
; #pragma unroll
;         for (int s = 0; s < 32; ++s) Z2[(size_t)(rbase + t0 + s) * 256 + blk * 64 + lane] = tobf(xl[s * 68 + lane] * siluf(bf1(gpv[s]))); }
	v_mul_f32_e32 v25, v0, v25
	v_mul_f32_e32 v0, 0xbfb8aa3b, v27
	s_addc_u32 s19, s33, s14
	v_exp_f32_e32 v43, v0
	s_add_u32 s14, s15, s88
	s_addc_u32 s15, s19, 0
	v_lshl_add_u64 v[18:19], s[14:15], 0, v[8:9]
	global_load_ushort v44, v[60:61], off offset:3392
	global_load_ushort v45, v[62:63], off offset:3392
	s_nop 0
	global_load_ushort v20, v[20:21], off offset:3392
	s_nop 0
	global_load_ushort v21, v[64:65], off offset:3392
	global_load_ushort v46, v[66:67], off offset:3392
	s_nop 0
	global_load_ushort v16, v[16:17], off offset:3392
	s_nop 0
	global_load_ushort v9, v[68:69], off offset:3392
	global_load_ushort v0, v[18:19], off offset:3392
	v_add_f32_e32 v18, 1.0, v43
	v_cvt_pk_bf16_f32 v17, v25, v1
	v_rcp_f32_e32 v25, v18
	v_lshl_add_u64 v[14:15], v[6:7], 0, s[88:89]
	s_lshl_b64 s[14:15], s[24:25], 9
	v_lshl_add_u64 v[18:19], v[14:15], 0, s[14:15]
	global_store_short v[18:19], v17, off
	v_mul_f32_e32 v18, v25, v27
	v_lshlrev_b32_e32 v25, 16, v71
	ds_read_b32 v17, v90 offset:272
	v_mul_f32_e32 v19, 0xbfb8aa3b, v25
	v_exp_f32_e32 v19, v19
	s_lshl_b64 s[14:15], s[26:27], 9
	v_lshlrev_b32_e32 v22, 16, v22
	s_waitcnt lgkmcnt(0)
	v_mul_f32_e32 v17, v18, v17
	v_add_f32_e32 v18, 1.0, v19
	v_rcp_f32_e32 v27, v18
	v_lshl_add_u64 v[18:19], v[14:15], 0, s[14:15]
	v_cvt_pk_bf16_f32 v17, v17, v1
	global_store_short v[18:19], v17, off
	v_mul_f32_e32 v18, v27, v25
	v_lshlrev_b32_e32 v25, 16, v72
	ds_read_b32 v17, v90 offset:544
	v_mul_f32_e32 v19, 0xbfb8aa3b, v25
	v_exp_f32_e32 v19, v19
	s_lshl_b64 s[14:15], s[20:21], 9
	v_readlane_b32 s21, v254, 47
	s_waitcnt lgkmcnt(0)
	v_mul_f32_e32 v17, v18, v17
	v_add_f32_e32 v18, 1.0, v19
	v_rcp_f32_e32 v27, v18
	v_lshl_add_u64 v[18:19], v[14:15], 0, s[14:15]
	v_cvt_pk_bf16_f32 v17, v17, v1
	global_store_short v[18:19], v17, off
	v_mul_f32_e32 v18, v27, v25
	v_lshlrev_b32_e32 v25, 16, v73
	ds_read_b32 v17, v90 offset:816
	v_mul_f32_e32 v19, 0xbfb8aa3b, v25
	v_exp_f32_e32 v19, v19
	s_lshl_b64 s[14:15], s[34:35], 9
	s_waitcnt lgkmcnt(0)
	v_mul_f32_e32 v17, v18, v17
	v_add_f32_e32 v18, 1.0, v19
	v_cvt_pk_bf16_f32 v17, v17, v1
	v_rcp_f32_e32 v27, v18
	v_lshl_add_u64 v[18:19], v[14:15], 0, s[14:15]
	global_store_short v[18:19], v17, off
	ds_read_b32 v17, v90 offset:1088
	v_mul_f32_e32 v19, 0xbfb8aa3b, v22
	v_exp_f32_e32 v19, v19
	v_mul_f32_e32 v18, v27, v25
	s_lshl_b64 s[14:15], s[28:29], 9
	s_waitcnt lgkmcnt(0)
	v_mul_f32_e32 v17, v18, v17
	v_add_f32_e32 v18, 1.0, v19
	v_rcp_f32_e32 v25, v18
	v_lshl_add_u64 v[18:19], v[14:15], 0, s[14:15]
	v_cvt_pk_bf16_f32 v17, v17, v1
	global_store_short v[18:19], v17, off
	v_mul_f32_e32 v18, v25, v22
	v_lshlrev_b32_e32 v22, 16, v23
	ds_read_b32 v17, v90 offset:1360
	v_mul_f32_e32 v19, 0xbfb8aa3b, v22
	v_exp_f32_e32 v19, v19
	s_lshl_b64 s[14:15], vcc, 9
	s_waitcnt lgkmcnt(0)
	v_mul_f32_e32 v17, v18, v17
	v_add_f32_e32 v18, 1.0, v19
	v_rcp_f32_e32 v23, v18
	v_lshl_add_u64 v[18:19], v[14:15], 0, s[14:15]
	v_cvt_pk_bf16_f32 v17, v17, v1
	global_store_short v[18:19], v17, off
	v_mul_f32_e32 v18, v23, v22
	v_lshlrev_b32_e32 v22, 16, v24
	ds_read_b32 v17, v90 offset:1632
	v_mul_f32_e32 v19, 0xbfb8aa3b, v22
	v_exp_f32_e32 v19, v19
	s_lshl_b64 s[14:15], s[80:81], 9
	s_waitcnt vmcnt(0)
	v_lshlrev_b32_e32 v20, 16, v20
	s_waitcnt lgkmcnt(0)
	v_mul_f32_e32 v17, v18, v17
	v_add_f32_e32 v18, 1.0, v19
	v_rcp_f32_e32 v23, v18
	v_lshl_add_u64 v[18:19], v[14:15], 0, s[14:15]
	v_cvt_pk_bf16_f32 v17, v17, v1
	global_store_short v[18:19], v17, off
	v_mul_f32_e32 v18, v23, v22
	v_lshlrev_b32_e32 v22, 16, v28
	ds_read_b32 v17, v90 offset:1904
	v_mul_f32_e32 v19, 0xbfb8aa3b, v22
	v_exp_f32_e32 v19, v19
	s_lshl_b64 s[14:15], s[78:79], 9
	v_lshlrev_b32_e32 v9, 16, v9
	s_waitcnt lgkmcnt(0)
	v_mul_f32_e32 v17, v18, v17
	v_add_f32_e32 v18, 1.0, v19
	v_rcp_f32_e32 v23, v18
	v_lshl_add_u64 v[18:19], v[14:15], 0, s[14:15]
	v_cvt_pk_bf16_f32 v17, v17, v1
	global_store_short v[18:19], v17, off
	v_mul_f32_e32 v18, v23, v22
	v_lshlrev_b32_e32 v22, 16, v29
	ds_read_b32 v17, v90 offset:2176
	v_mul_f32_e32 v19, 0xbfb8aa3b, v22
	v_exp_f32_e32 v19, v19
	s_lshl_b64 s[14:15], s[74:75], 9
	v_lshlrev_b32_e32 v0, 16, v0
	s_waitcnt lgkmcnt(0)
	v_mul_f32_e32 v17, v18, v17
	v_add_f32_e32 v18, 1.0, v19
	v_rcp_f32_e32 v23, v18
	v_lshl_add_u64 v[18:19], v[14:15], 0, s[14:15]
	v_cvt_pk_bf16_f32 v17, v17, v1
	global_store_short v[18:19], v17, off
	v_mul_f32_e32 v18, v23, v22
	v_lshlrev_b32_e32 v22, 16, v30
	ds_read_b32 v17, v90 offset:2448
	v_mul_f32_e32 v19, 0xbfb8aa3b, v22
	v_exp_f32_e32 v19, v19
	s_lshl_b64 s[14:15], s[68:69], 9
	s_waitcnt lgkmcnt(0)
	v_mul_f32_e32 v17, v18, v17
	v_add_f32_e32 v18, 1.0, v19
	v_rcp_f32_e32 v23, v18
	v_lshl_add_u64 v[18:19], v[14:15], 0, s[14:15]
	v_cvt_pk_bf16_f32 v17, v17, v1
	global_store_short v[18:19], v17, off
	v_mul_f32_e32 v18, v23, v22
	v_lshlrev_b32_e32 v22, 16, v31
	ds_read_b32 v17, v90 offset:2720
	v_mul_f32_e32 v19, 0xbfb8aa3b, v22
	v_exp_f32_e32 v19, v19
	s_lshl_b64 s[14:15], s[66:67], 9
	s_waitcnt lgkmcnt(0)
	v_mul_f32_e32 v17, v18, v17
	v_add_f32_e32 v18, 1.0, v19
	v_rcp_f32_e32 v23, v18
	v_lshl_add_u64 v[18:19], v[14:15], 0, s[14:15]
	v_cvt_pk_bf16_f32 v17, v17, v1
	global_store_short v[18:19], v17, off
	v_mul_f32_e32 v18, v23, v22
	v_lshlrev_b32_e32 v22, 16, v32
	ds_read_b32 v17, v90 offset:2992
	v_mul_f32_e32 v19, 0xbfb8aa3b, v22
	v_exp_f32_e32 v19, v19
	s_lshl_b64 s[14:15], s[62:63], 9
	s_waitcnt lgkmcnt(0)
	v_mul_f32_e32 v17, v18, v17
	v_add_f32_e32 v18, 1.0, v19
	v_rcp_f32_e32 v23, v18
	v_lshl_add_u64 v[18:19], v[14:15], 0, s[14:15]
	v_cvt_pk_bf16_f32 v17, v17, v1
	global_store_short v[18:19], v17, off
	v_mul_f32_e32 v18, v23, v22
	v_lshlrev_b32_e32 v22, 16, v33
	ds_read_b32 v17, v90 offset:3264
	v_mul_f32_e32 v19, 0xbfb8aa3b, v22
	v_exp_f32_e32 v19, v19
	s_lshl_b64 s[14:15], s[58:59], 9
	s_waitcnt lgkmcnt(0)
; __device__ __forceinline__ float bf1(bf16_t v) { return __uint_as_float(((unsigned)v) << 16); }
; __device__ __forceinline__ bf16_t tobf(float f) { return (bf16_t)(cvt_pk_bf16(f, 0.f) & 0xffffu); }
; __device__ __forceinline__ float siluf(float x) { return x * __builtin_amdgcn_rcpf(1.f + __expf(-x)); }
; template <bool PASS2> ...
;     ...
;         for (int s = 0; s < 32; ++s) gpv[s] = P[(size_t)(rbase + t0 + s) * INP + OFF_GATE + 2 * 256 + blk * 64 + lane];
; #pragma unroll
;         for (int s = 0; s < 32; ++s) Z2[(size_t)(rbase + t0 + s) * 256 + blk * 64 + lane] = tobf(xl[s * 68 + lane] * siluf(bf1(gpv[s]))); }
	v_mul_f32_e32 v17, v18, v17
	v_add_f32_e32 v18, 1.0, v19
	v_rcp_f32_e32 v23, v18
	v_lshl_add_u64 v[18:19], v[14:15], 0, s[14:15]
	v_cvt_pk_bf16_f32 v17, v17, v1
	global_store_short v[18:19], v17, off
	v_mul_f32_e32 v18, v23, v22
	v_lshlrev_b32_e32 v22, 16, v34
	ds_read_b32 v17, v90 offset:3536
	v_mul_f32_e32 v19, 0xbfb8aa3b, v22
	v_exp_f32_e32 v19, v19
	s_lshl_b64 s[14:15], s[56:57], 9
	s_waitcnt lgkmcnt(0)
	v_mul_f32_e32 v17, v18, v17
	v_add_f32_e32 v18, 1.0, v19
	v_rcp_f32_e32 v23, v18
	v_lshl_add_u64 v[18:19], v[14:15], 0, s[14:15]
	v_cvt_pk_bf16_f32 v17, v17, v1
	global_store_short v[18:19], v17, off
	v_mul_f32_e32 v18, v23, v22
	v_lshlrev_b32_e32 v22, 16, v35
	ds_read_b32 v17, v90 offset:3808
	v_mul_f32_e32 v19, 0xbfb8aa3b, v22
	v_exp_f32_e32 v19, v19
	s_lshl_b64 s[14:15], s[54:55], 9
	s_waitcnt lgkmcnt(0)
	v_mul_f32_e32 v17, v18, v17
	v_add_f32_e32 v18, 1.0, v19
	v_rcp_f32_e32 v23, v18
	v_lshl_add_u64 v[18:19], v[14:15], 0, s[14:15]
	v_cvt_pk_bf16_f32 v17, v17, v1
	global_store_short v[18:19], v17, off
	v_mul_f32_e32 v18, v23, v22
	v_lshlrev_b32_e32 v22, 16, v36
	ds_read_b32 v17, v90 offset:4080
	v_mul_f32_e32 v19, 0xbfb8aa3b, v22
	v_exp_f32_e32 v19, v19
	s_lshl_b64 s[14:15], s[52:53], 9
	s_waitcnt lgkmcnt(0)
	v_mul_f32_e32 v17, v18, v17
	v_add_f32_e32 v18, 1.0, v19
	v_rcp_f32_e32 v23, v18
	v_lshl_add_u64 v[18:19], v[14:15], 0, s[14:15]
	v_cvt_pk_bf16_f32 v17, v17, v1
	global_store_short v[18:19], v17, off
	v_mul_f32_e32 v18, v23, v22
	v_lshlrev_b32_e32 v22, 16, v37
	ds_read_b32 v17, v90 offset:4352
	v_mul_f32_e32 v19, 0xbfb8aa3b, v22
	v_exp_f32_e32 v19, v19
	s_lshl_b64 s[14:15], s[50:51], 9
	s_waitcnt lgkmcnt(0)
	v_mul_f32_e32 v17, v18, v17
	v_add_f32_e32 v18, 1.0, v19
	v_rcp_f32_e32 v23, v18
	v_lshl_add_u64 v[18:19], v[14:15], 0, s[14:15]
	v_cvt_pk_bf16_f32 v17, v17, v1
	global_store_short v[18:19], v17, off
	v_mul_f32_e32 v18, v23, v22
	v_lshlrev_b32_e32 v22, 16, v38
	ds_read_b32 v17, v90 offset:4624
	v_mul_f32_e32 v19, 0xbfb8aa3b, v22
	v_exp_f32_e32 v19, v19
	s_lshl_b64 s[14:15], s[48:49], 9
	s_waitcnt lgkmcnt(0)
	v_mul_f32_e32 v17, v18, v17
	v_add_f32_e32 v18, 1.0, v19
	v_rcp_f32_e32 v23, v18
	v_lshl_add_u64 v[18:19], v[14:15], 0, s[14:15]
	v_cvt_pk_bf16_f32 v17, v17, v1
	global_store_short v[18:19], v17, off
	v_mul_f32_e32 v18, v23, v22
	v_lshlrev_b32_e32 v22, 16, v39
	ds_read_b32 v17, v90 offset:4896
	v_mul_f32_e32 v19, 0xbfb8aa3b, v22
	v_exp_f32_e32 v19, v19
	s_lshl_b64 s[14:15], s[46:47], 9
	s_waitcnt lgkmcnt(0)
	v_mul_f32_e32 v17, v18, v17
	v_add_f32_e32 v18, 1.0, v19
	v_rcp_f32_e32 v23, v18
	v_lshl_add_u64 v[18:19], v[14:15], 0, s[14:15]
	v_cvt_pk_bf16_f32 v17, v17, v1
	global_store_short v[18:19], v17, off
	v_mul_f32_e32 v18, v23, v22
	v_lshlrev_b32_e32 v22, 16, v40
	ds_read_b32 v17, v90 offset:5168
	v_mul_f32_e32 v19, 0xbfb8aa3b, v22
	v_exp_f32_e32 v19, v19
	s_lshl_b64 s[14:15], s[44:45], 9
	s_waitcnt lgkmcnt(0)
	v_mul_f32_e32 v17, v18, v17
	v_add_f32_e32 v18, 1.0, v19
	v_rcp_f32_e32 v23, v18
	v_lshl_add_u64 v[18:19], v[14:15], 0, s[14:15]
	v_cvt_pk_bf16_f32 v17, v17, v1
	global_store_short v[18:19], v17, off
	v_mul_f32_e32 v18, v23, v22
	v_lshlrev_b32_e32 v22, 16, v41
	ds_read_b32 v17, v90 offset:5440
	v_mul_f32_e32 v19, 0xbfb8aa3b, v22
	v_exp_f32_e32 v19, v19
	s_lshl_b64 s[14:15], s[42:43], 9
	s_waitcnt lgkmcnt(0)
	v_mul_f32_e32 v17, v18, v17
	v_add_f32_e32 v18, 1.0, v19
	v_rcp_f32_e32 v23, v18
	v_lshl_add_u64 v[18:19], v[14:15], 0, s[14:15]
	v_cvt_pk_bf16_f32 v17, v17, v1
	global_store_short v[18:19], v17, off
	v_mul_f32_e32 v18, v23, v22
	v_lshlrev_b32_e32 v22, 16, v42
	ds_read_b32 v17, v90 offset:5712
	v_mul_f32_e32 v19, 0xbfb8aa3b, v22
	v_exp_f32_e32 v19, v19
	s_lshl_b64 s[14:15], s[40:41], 9
	s_waitcnt lgkmcnt(0)
	v_mul_f32_e32 v17, v18, v17
	v_add_f32_e32 v18, 1.0, v19
	v_rcp_f32_e32 v23, v18
	v_lshl_add_u64 v[18:19], v[14:15], 0, s[14:15]
	v_cvt_pk_bf16_f32 v17, v17, v1
	global_store_short v[18:19], v17, off
	v_mul_f32_e32 v18, v23, v22
	v_lshlrev_b32_e32 v22, 16, v26
	ds_read_b32 v17, v90 offset:5984
	v_mul_f32_e32 v19, 0xbfb8aa3b, v22
	v_exp_f32_e32 v19, v19
	s_lshl_b64 s[14:15], s[38:39], 9
	s_waitcnt lgkmcnt(0)
; __device__ __forceinline__ float bf1(bf16_t v) { return __uint_as_float(((unsigned)v) << 16); }
; __device__ __forceinline__ bf16_t tobf(float f) { return (bf16_t)(cvt_pk_bf16(f, 0.f) & 0xffffu); }
; __device__ __forceinline__ float siluf(float x) { return x * __builtin_amdgcn_rcpf(1.f + __expf(-x)); }
; template <bool PASS2> ...
;     ...
;         for (int s = 0; s < 32; ++s) gpv[s] = P[(size_t)(rbase + t0 + s) * INP + OFF_GATE + 2 * 256 + blk * 64 + lane];
; #pragma unroll
;         for (int s = 0; s < 32; ++s) Z2[(size_t)(rbase + t0 + s) * 256 + blk * 64 + lane] = tobf(xl[s * 68 + lane] * siluf(bf1(gpv[s]))); }
; __global__ void __launch_bounds__(512, 2) fwd_kernel(KArgs a) {
;     ...
;             { IDS; const int ncc = wctx ? NCH : 64, nL2 = HB * ncc * 4; for (int t = gw, k_ = 0; t < nL2; t = NGW != 2048 ? t + NGW : (((gw & 7) == 0 && k_ == 0) ? NGW + (gw >> 3) : nL2), ++k_) { const int blk = t & 3, cc = (t >> 2) % ncc, b = (t >> 2) / ncc; const int t2 = ((b * NCH + (wctx ? cc : cc + 8)) << 2) | blk;
;                 lru_task<true>(t2, l, a.in[23], a.in[24], a.in[25], a.in[27], a.in[29], wscr, P, WLRU, LRA, LRB, LRH, LAB, Z2, lane); } }
	v_mul_f32_e32 v17, v18, v17
	v_add_f32_e32 v18, 1.0, v19
	v_rcp_f32_e32 v23, v18
	v_lshl_add_u64 v[18:19], v[14:15], 0, s[14:15]
	v_cvt_pk_bf16_f32 v17, v17, v1
	global_store_short v[18:19], v17, off
	v_mul_f32_e32 v18, v23, v22
	v_lshlrev_b32_e32 v22, 16, v44
	ds_read_b32 v17, v90 offset:6256
	v_mul_f32_e32 v19, 0xbfb8aa3b, v22
	v_exp_f32_e32 v19, v19
	s_lshl_b64 s[14:15], s[36:37], 9
	s_waitcnt lgkmcnt(0)
	v_mul_f32_e32 v17, v18, v17
	v_add_f32_e32 v18, 1.0, v19
	v_rcp_f32_e32 v23, v18
	v_lshl_add_u64 v[18:19], v[14:15], 0, s[14:15]
	v_cvt_pk_bf16_f32 v17, v17, v1
	global_store_short v[18:19], v17, off
	v_mul_f32_e32 v18, v23, v22
	v_lshlrev_b32_e32 v22, 16, v45
	ds_read_b32 v17, v90 offset:6528
	v_mul_f32_e32 v19, 0xbfb8aa3b, v22
	v_exp_f32_e32 v19, v19
	s_lshl_b64 s[14:15], s[22:23], 9
	s_waitcnt lgkmcnt(0)
	v_mul_f32_e32 v17, v18, v17
	v_add_f32_e32 v18, 1.0, v19
	v_cvt_pk_bf16_f32 v17, v17, v1
	v_rcp_f32_e32 v23, v18
	v_lshl_add_u64 v[18:19], v[14:15], 0, s[14:15]
	global_store_short v[18:19], v17, off
	ds_read_b32 v17, v90 offset:6800
	v_mul_f32_e32 v19, 0xbfb8aa3b, v20
	v_exp_f32_e32 v19, v19
	v_mul_f32_e32 v18, v23, v22
	s_lshl_b64 s[14:15], s[30:31], 9
	s_waitcnt lgkmcnt(0)
	v_mul_f32_e32 v17, v18, v17
	v_add_f32_e32 v18, 1.0, v19
	v_rcp_f32_e32 v22, v18
	v_lshl_add_u64 v[18:19], v[14:15], 0, s[14:15]
	v_cvt_pk_bf16_f32 v17, v17, v1
	global_store_short v[18:19], v17, off
	v_mul_f32_e32 v18, v22, v20
	v_lshlrev_b32_e32 v20, 16, v21
	ds_read_b32 v17, v90 offset:7072
	v_mul_f32_e32 v19, 0xbfb8aa3b, v20
	v_exp_f32_e32 v19, v19
	s_lshl_b64 s[14:15], s[96:97], 9
	s_waitcnt lgkmcnt(0)
	v_mul_f32_e32 v17, v18, v17
	v_add_f32_e32 v18, 1.0, v19
	v_rcp_f32_e32 v21, v18
	v_lshl_add_u64 v[18:19], v[14:15], 0, s[14:15]
	v_cvt_pk_bf16_f32 v17, v17, v1
	global_store_short v[18:19], v17, off
	v_mul_f32_e32 v18, v21, v20
	v_lshlrev_b32_e32 v20, 16, v46
	ds_read_b32 v17, v90 offset:7344
	v_mul_f32_e32 v19, 0xbfb8aa3b, v20
	v_exp_f32_e32 v19, v19
	s_lshl_b64 s[14:15], s[82:83], 9
	s_waitcnt lgkmcnt(0)
	v_mul_f32_e32 v17, v18, v17
	v_add_f32_e32 v18, 1.0, v19
	v_rcp_f32_e32 v21, v18
	v_lshl_add_u64 v[18:19], v[14:15], 0, s[14:15]
	v_cvt_pk_bf16_f32 v17, v17, v1
	global_store_short v[18:19], v17, off
	v_lshlrev_b32_e32 v19, 16, v16
	ds_read_b32 v17, v90 offset:7616
	v_mul_f32_e32 v16, 0xbfb8aa3b, v19
	v_exp_f32_e32 v16, v16
	v_mul_f32_e32 v18, v21, v20
	s_lshl_b64 s[14:15], s[76:77], 9
	s_waitcnt lgkmcnt(0)
	v_mul_f32_e32 v17, v18, v17
	v_add_f32_e32 v16, 1.0, v16
	v_cvt_pk_bf16_f32 v18, v17, v1
	v_rcp_f32_e32 v20, v16
	v_lshl_add_u64 v[16:17], v[14:15], 0, s[14:15]
	global_store_short v[16:17], v18, off
	ds_read_b32 v16, v90 offset:7888
	v_mul_f32_e32 v18, 0xbfb8aa3b, v9
	v_exp_f32_e32 v18, v18
	v_mul_f32_e32 v17, v20, v19
	s_lshl_b64 s[14:15], s[72:73], 9
	s_waitcnt lgkmcnt(0)
	v_mul_f32_e32 v16, v17, v16
	v_cvt_pk_bf16_f32 v19, v16, v1
	v_add_f32_e32 v16, 1.0, v18
	v_rcp_f32_e32 v18, v16
	v_lshl_add_u64 v[16:17], v[14:15], 0, s[14:15]
	global_store_short v[16:17], v19, off
	ds_read_b32 v16, v90 offset:8160
	v_mul_f32_e32 v17, 0xbfb8aa3b, v0
	v_exp_f32_e32 v17, v17
	v_mul_f32_e32 v9, v18, v9
	s_lshl_b64 s[14:15], s[60:61], 9
	s_waitcnt lgkmcnt(0)
	v_mul_f32_e32 v9, v9, v16
	v_add_f32_e32 v16, 1.0, v17
	v_readlane_b32 s60, v253, 51
	v_cvt_pk_bf16_f32 v9, v9, v1
	ds_read_b32 v18, v90 offset:8432
	v_rcp_f32_e32 v19, v16
	v_lshl_add_u64 v[16:17], v[14:15], 0, s[14:15]
	s_lshl_b64 s[14:15], s[64:65], 9
	s_add_i32 s19, s91, s60
	s_cmp_eq_u32 s7, 0
	v_lshl_add_u64 v[14:15], v[14:15], 0, s[14:15]
	s_cselect_b64 s[14:15], -1, 0
	s_and_b64 s[14:15], s[4:5], s[14:15]
	v_mul_f32_e32 v0, v19, v0
	s_and_b64 s[14:15], s[14:15], exec
	s_waitcnt lgkmcnt(0)
	v_mul_f32_e32 v0, v0, v18
	v_readlane_b32 s14, v253, 25
	global_store_short v[16:17], v9, off
	v_cvt_pk_bf16_f32 v0, v0, v1
	global_store_short v[14:15], v0, off
	v_readlane_b32 s15, v253, 26
	s_cselect_b32 s20, s18, s21
	s_and_b64 s[14:15], s[14:15], exec
	s_waitcnt lgkmcnt(0)
	s_cselect_b32 s91, s20, s19
	s_add_i32 s7, s7, 1
	s_cmp_ge_i32 s91, s21
	v_readlane_b32 s61, v253, 52
	s_cbranch_scc1 .LBB0_1231

; template <bool PASS2> ...
;     ...
;     for (int d = 0; d < 2; ++d) {
;         bf16x8 wfa[4][2], wfx[4][2]; float pba[4], pbx[4], plm[4], phin[4]; unsigned pkv[4][2][4];
;         unsigned* labd = LAB + ((size_t)d * MH + rbase + t0 + fq * 4) * 256 + blk * 64 + fr;
; #pragma unroll
;         for (int cb = 0; cb < 4; ++cb) {
;             const int chn = blk * 64 + cb * 16 + fr;
;             if (!PASS2) {
;                 const bf16_t* wa = WLRU + ((size_t)(((l * 2 + d) * 2 + 0) * 4 + blk) * 64 + cb * 16 + fr) * 64 + fq * 8;
; #pragma unroll
;                 for (int ks = 0; ks < 2; ++ks) { wfa[cb][ks] = asfrag(ld8(wa + ks * 32)); wfx[cb][ks] = asfrag(ld8(wa + 4 * 4096 + ks * 32)); }
;                 pba[cb] = b_a[(l * 2 + d) * 256 + chn]; pbx[cb] = b_x[(l * 2 + d) * 256 + chn]; plm[cb] = lam[(l * 2 + d) * 256 + chn];
;             } else {
;                 phin[cb] = LRH[((size_t)(b * NCH + c) * 2 + d) * 256 + chn];
; #pragma unroll
;                 for (int tb = 0; tb < 2; ++tb)
; #pragma unroll
;                     for (int q = 0; q < 4; ++q) pkv[cb][tb][q] = labd[(size_t)(tb * 16 + q) * 256 + cb * 16];
;             }
;         }
; #pragma unroll
;         for (int cb = 0; cb < 4; ++cb) {
;             const int chn = blk * 64 + cb * 16 + fr;
;             float av[2][4], bv[2][4], Ap[2], Bp[2];
;             if (!PASS2) {
;                 f32x4 ga[2], gx[2];
;                 ga[0] = ga[1] = gx[0] = gx[1] = (f32x4){0.f, 0.f, 0.f, 0.f};
; #pragma unroll
;                 for (int ks = 0; ks < 2; ++ks) {
; #pragma unroll
;                     for (int tb = 0; tb < 2; ++tb) { ga[tb] = MFMA16(af[tb][ks], wfa[cb][ks], ga[tb]); gx[tb] = MFMA16(af[tb][ks], wfx[cb][ks], gx[tb]); } }
;                 const float ba = pba[cb], bx = pbx[cb], sp = log1pf(__expf(-plm[cb]));
; #pragma unroll
;                 for (int tb = 0; tb < 2; ++tb)
; #pragma unroll
;                     for (int q = 0; q < 4; ++q) { const float xv = xl[(tb * 16 + fq * 4 + q) * 68 + cb * 16 + fr];
;                         const float r = sigm(ga[tb][q] + ba), ig = sigm(gx[tb][q] + bx), la = -8.f * r * sp;
;                         const float aa = __expf(la), om = (1.f - aa) * (1.f + aa), bb = __builtin_amdgcn_sqrtf(om) * (ig * xv);
;                         const unsigned pk = cvt_pk_bf16(la, bb);
;                         labd[(size_t)(tb * 16 + q) * 256 + cb * 16] = pk;
.LBB0_1166:
	s_mul_i32 s88, s20, 0x4800
	v_lshl_add_u64 v[52:53], v[16:17], 0, s[88:89]
	v_lshlrev_b64 v[52:53], 10, v[52:53]
	v_lshl_add_u64 v[54:55], v[14:15], 0, v[52:53]
	s_lshl_b64 s[20:21], s[20:21], 10
	v_lshl_add_u64 v[58:59], v[20:21], 0, s[20:21]
	v_add_co_u32_e32 v96, vcc, s0, v54
	s_xor_b64 s[20:21], s[68:69], -1
	s_nop 0
	v_addc_co_u32_e32 v97, vcc, 0, v55, vcc
	global_load_dword v56, v[58:59], off
	global_load_dword v53, v[96:97], off
	global_load_dword v64, v[58:59], off offset:64
	global_load_dword v60, v[96:97], off offset:64
	global_load_dword v72, v[58:59], off offset:128
	global_load_dword v68, v[96:97], off offset:128
	global_load_dword v9, v[96:97], off offset:192
	global_load_dword v0, v[58:59], off offset:192
	global_load_dword v52, v[54:55], off
	s_nop 0
	global_load_dword v58, v[54:55], off offset:1024
	global_load_dword v67, v[54:55], off offset:64
	global_load_dword v66, v[54:55], off offset:1088
	global_load_dword v75, v[54:55], off offset:128
	global_load_dword v74, v[54:55], off offset:1152
	global_load_dword v80, v[54:55], off offset:1216
	global_load_dword v81, v[54:55], off offset:192
	global_load_dword v59, v[54:55], off offset:2048
	global_load_dword v93, v[54:55], off offset:3072
	global_load_dword v92, v[54:55], off offset:2112
	global_load_dword v65, v[54:55], off offset:3136
	global_load_dword v83, v[54:55], off offset:2176
	global_load_dword v73, v[54:55], off offset:3200
	global_load_dword v79, v[54:55], off offset:3264
	global_load_dword v82, v[54:55], off offset:2240
	global_load_dword v94, v[96:97], off offset:1024
	s_nop 0
	global_load_dword v55, v[96:97], off offset:2048
	global_load_dword v63, v[96:97], off offset:1088
	global_load_dword v62, v[96:97], off offset:2112
	global_load_dword v71, v[96:97], off offset:1152
	global_load_dword v70, v[96:97], off offset:2176
	global_load_dword v77, v[96:97], off offset:2240
	global_load_dword v78, v[96:97], off offset:1216
	global_load_dword v54, v[96:97], off offset:3072
	global_load_dword v61, v[96:97], off offset:3136
	global_load_dword v69, v[96:97], off offset:3200
	global_load_dword v76, v[96:97], off offset:3264
	s_and_b64 vcc, exec, s[20:21]
	s_mov_b64 s[22:23], -1
	s_waitcnt vmcnt(0) lgkmcnt(0)
	v_lshlrev_b32_e32 v95, 16, v52
	v_and_b32_e32 v57, 0xffff0000, v52
	v_lshlrev_b32_e32 v52, 16, v58
	v_mul_f32_e32 v95, 0x3fb8aa3b, v95
	v_mul_f32_e32 v52, 0x3fb8aa3b, v52
	v_exp_f32_e32 v104, v95
	v_exp_f32_e32 v103, v52
	v_and_b32_e32 v58, 0xffff0000, v58
	v_lshlrev_b32_e32 v96, 16, v59
	v_mul_f32_e32 v96, 0x3fb8aa3b, v96
	v_exp_f32_e32 v102, v96
	v_and_b32_e32 v59, 0xffff0000, v59
	v_and_b32_e32 v101, 0xffff0000, v93
	s_cbranch_vccz .LBB0_1168
	v_fma_f32 v52, v102, v101, v59
	v_fma_f32 v52, v103, v52, v58
	v_fma_f32 v52, v104, v52, v57
	s_mov_b64 s[22:23], 0

; __device__ __forceinline__ unsigned cvt_pk_bf16(float lo, float hi) { unsigned r; asm volatile("v_cvt_pk_bf16_f32 %0, %1, %2" : "=v"(r) : "v"(lo), "v"(hi)); return r; }
; __device__ __forceinline__ float gelu_tanh(float x) { const float u = 0.7978845608028654f * (x + 0.044715f * x * x * x); return x * sigm(2.f * u); }
; #define UNPK8(VV_, XX_) float XX_[8] = {bflo((VV_).x), bfhi((VV_).x), bflo((VV_).y), bfhi((VV_).y), bflo((VV_).z), bfhi((VV_).z), bflo((VV_).w), bfhi((VV_).w)}
; __device__ __forceinline__ void glu_task(int t, int l, const float* s5d, const bf16_t* P, const bf16_t* YB, const bf16_t* WGLU, bf16_t* Z1, int fr, int fq) {
;     const int cb0 = (t & 3) * 4; const size_t row0 = (size_t)((t >> 2) * 32 + fr);
;     bf16x8 bfr[2][8];
; #pragma unroll
;     for (int tb = 0; tb < 2; ++tb) { const size_t row = row0 + tb * 16;
; #pragma unroll
;         for (int ks = 0; ks < 8; ++ks) { const int k0 = ks * 32 + fq * 8; const u32x4 yw = ld8(YB + row * 256 + k0), uw = ld8(P + row * INP + OFF_S5 + k0);
;             const f32x4 d0 = *(const f32x4*)(s5d + l * 256 + k0), d1 = *(const f32x4*)(s5d + l * 256 + k0 + 4); UNPK8(yw, y); UNPK8(uw, u); u32x4 o;
;             o.x = cvt_pk_bf16(gelu_tanh(y[0] + d0[0] * u[0]), gelu_tanh(y[1] + d0[1] * u[1])); o.y = cvt_pk_bf16(gelu_tanh(y[2] + d0[2] * u[2]), gelu_tanh(y[3] + d0[3] * u[3]));
;             o.z = cvt_pk_bf16(gelu_tanh(y[4] + d1[0] * u[4]), gelu_tanh(y[5] + d1[1] * u[5])); o.w = cvt_pk_bf16(gelu_tanh(y[6] + d1[2] * u[6]), gelu_tanh(y[7] + d1[3] * u[7]));
;             bfr[tb][ks] = asfrag(o); } }
.LBB0_1282:
	s_lshl_b32 s5, s20, 3
	s_andn2_b32 s5, s5, 31
	v_or_b32_e32 v2, s5, v174
	v_ashrrev_i32_e32 v3, 31, v2
	v_lshlrev_b64 v[114:115], 9, v[2:3]
	v_lshl_add_u64 v[70:71], s[38:39], 0, v[114:115]
	v_mov_b64_e32 v[4:5], s[36:37]
	v_mad_i64_i32 v[72:73], s[6:7], v2, s84, v[4:5]
	v_lshl_add_u64 v[34:35], v[70:71], 0, v[0:1]
	v_lshl_add_u64 v[36:37], v[72:73], 0, v[0:1]
	ds_read_b128 v[14:17], v246 offset:16
	ds_read_b128 v[18:21], v246
	v_or_b32_e32 v138, 0x2000, v114
	v_mov_b32_e32 v139, v115
	v_lshl_add_u64 v[74:75], s[38:39], 0, v[138:139]
	s_mov_b64 s[6:7], 0x22000
	v_lshl_add_u64 v[76:77], v[72:73], 0, s[6:7]
	v_lshl_add_u64 v[66:67], v[74:75], 0, v[0:1]
	v_lshl_add_u64 v[68:69], v[76:77], 0, v[0:1]
	s_lshl_b32 s1, s20, 6
	s_and_b32 s5, s1, 0xc0
	v_or_b32_e32 v178, s5, v175
	v_lshlrev_b32_e32 v158, 1, v178
	v_mov_b32_e32 v159, v1
	v_lshl_add_u64 v[70:71], v[70:71], 0, v[158:159]
	v_lshl_add_u64 v[72:73], v[72:73], 0, v[158:159]
	v_lshlrev_b32_e32 v178, 2, v178
	s_add_i32 s1, s20, s60
	global_load_dwordx4 v[98:101], v[34:35], off
	global_load_dwordx4 v[102:105], v[36:37], off offset:320
	global_load_dwordx4 v[106:109], v[34:35], off offset:64
	global_load_dwordx4 v[110:113], v[36:37], off offset:384
	global_load_dwordx4 v[118:121], v[34:35], off offset:128
	global_load_dwordx4 v[122:125], v[36:37], off offset:448
	global_load_dwordx4 v[126:129], v[34:35], off offset:192
	global_load_dwordx4 v[130:133], v[36:37], off offset:512
	global_load_dwordx4 v[140:143], v[34:35], off offset:256
	global_load_dwordx4 v[144:147], v[36:37], off offset:576
	global_load_dwordx4 v[160:163], v[34:35], off offset:320
	global_load_dwordx4 v[164:167], v[36:37], off offset:640
	global_load_dwordx4 v[180:183], v[34:35], off offset:384
	global_load_dwordx4 v[184:187], v[36:37], off offset:704
	global_load_dwordx4 v[214:217], v[34:35], off offset:448
	global_load_dwordx4 v[218:221], v[36:37], off offset:768
	global_load_dwordx4 v[222:225], v[66:67], off
	global_load_dwordx4 v[226:229], v[68:69], off offset:320
	global_load_dwordx4 v[230:233], v[66:67], off offset:64
	global_load_dwordx4 v[234:237], v[68:69], off offset:384
	global_load_dwordx4 v[238:241], v[66:67], off offset:128
	global_load_dwordx4 v[242:245], v[68:69], off offset:448
	global_load_dwordx4 v[168:171], v[66:67], off offset:192
	global_load_dwordx4 v[188:191], v[68:69], off offset:512
	s_waitcnt vmcnt(22) lgkmcnt(0)
	v_mov_b32_e32 v2, v98
	v_mov_b32_e32 v3, v99
	v_mov_b32_e32 v4, v100
	v_mov_b32_e32 v5, v101
	v_mov_b32_e32 v6, v102
	v_mov_b32_e32 v7, v103
	v_mov_b32_e32 v8, v104
	v_mov_b32_e32 v9, v105
	global_load_dwordx4 v[98:101], v[66:67], off offset:256
	global_load_dwordx4 v[102:105], v[68:69], off offset:576
	v_lshlrev_b32_e32 v26, 16, v6
	v_lshlrev_b32_e32 v22, 16, v2
	v_and_b32_e32 v2, 0xffff0000, v2
	v_and_b32_e32 v6, 0xffff0000, v6
	v_fmac_f32_e32 v2, v19, v6
	v_mul_f32_e32 v6, 0x3d372713, v2
	v_mul_f32_e32 v6, v2, v6
	v_fma_f32 v6, v2, v6, v2
	v_mul_f32_e32 v6, 0x3f4c422a, v6
	v_add_f32_e32 v6, v6, v6
	v_mul_f32_e32 v6, 0xbfb8aa3b, v6
	v_exp_f32_e32 v6, v6
	v_lshlrev_b32_e32 v23, 16, v3
	v_and_b32_e32 v3, 0xffff0000, v3
	v_lshlrev_b32_e32 v27, 16, v7
	v_add_f32_e32 v6, 1.0, v6
	v_rcp_f32_e32 v6, v6
	v_and_b32_e32 v7, 0xffff0000, v7
	v_fmac_f32_e32 v23, v20, v27
	v_fmac_f32_e32 v3, v21, v7
	v_fmac_f32_e32 v22, v18, v26
	v_mul_f32_e32 v2, v2, v6
	v_mul_f32_e32 v6, 0x3d372713, v23
	v_mul_f32_e32 v7, 0x3d372713, v3
	v_mul_f32_e32 v18, 0x3d372713, v22
	v_mul_f32_e32 v6, v23, v6
	v_mul_f32_e32 v7, v3, v7
	v_mul_f32_e32 v18, v22, v18
	v_fma_f32 v6, v23, v6, v23
	v_fma_f32 v7, v3, v7, v3
	v_fma_f32 v18, v22, v18, v22
	v_mul_f32_e32 v6, 0x3f4c422a, v6
	v_mul_f32_e32 v7, 0x3f4c422a, v7
	v_mul_f32_e32 v18, 0x3f4c422a, v18
	v_add_f32_e32 v6, v6, v6
	v_add_f32_e32 v7, v7, v7
	v_add_f32_e32 v18, v18, v18
	v_mul_f32_e32 v6, 0xbfb8aa3b, v6
	v_mul_f32_e32 v7, 0xbfb8aa3b, v7
	v_mul_f32_e32 v18, 0xbfb8aa3b, v18
	v_exp_f32_e32 v6, v6
	v_exp_f32_e32 v7, v7
	v_exp_f32_e32 v18, v18
	v_lshlrev_b32_e32 v24, 16, v4
	v_add_f32_e32 v6, 1.0, v6
	v_add_f32_e32 v7, 1.0, v7
	v_add_f32_e32 v18, 1.0, v18
	v_rcp_f32_e32 v6, v6
	v_rcp_f32_e32 v7, v7
	v_rcp_f32_e32 v18, v18
	v_and_b32_e32 v4, 0xffff0000, v4
	v_lshlrev_b32_e32 v28, 16, v8
	v_and_b32_e32 v8, 0xffff0000, v8
	v_mul_f32_e32 v6, v23, v6
	v_mul_f32_e32 v3, v3, v7
	v_fmac_f32_e32 v24, v14, v28
	v_fmac_f32_e32 v4, v15, v8
	v_mul_f32_e32 v18, v22, v18
	v_cvt_pk_bf16_f32 v2, v18, v2
	v_cvt_pk_bf16_f32 v3, v6, v3
	v_mul_f32_e32 v6, 0x3d372713, v24
	v_mul_f32_e32 v7, 0x3d372713, v4
	v_mul_f32_e32 v6, v24, v6
	v_mul_f32_e32 v7, v4, v7
	v_fma_f32 v6, v24, v6, v24
	v_fma_f32 v7, v4, v7, v4
	v_mul_f32_e32 v6, 0x3f4c422a, v6
	v_mul_f32_e32 v7, 0x3f4c422a, v7
	v_add_f32_e32 v6, v6, v6
	v_add_f32_e32 v7, v7, v7
	v_mul_f32_e32 v6, 0xbfb8aa3b, v6
	v_mul_f32_e32 v7, 0xbfb8aa3b, v7
	v_exp_f32_e32 v6, v6
	v_exp_f32_e32 v7, v7
	v_lshlrev_b32_e32 v25, 16, v5
	v_and_b32_e32 v5, 0xffff0000, v5
	v_add_f32_e32 v6, 1.0, v6
	v_add_f32_e32 v7, 1.0, v7
	v_rcp_f32_e32 v6, v6
	v_rcp_f32_e32 v7, v7
	v_lshlrev_b32_e32 v29, 16, v9
	v_and_b32_e32 v9, 0xffff0000, v9
	v_mul_f32_e32 v6, v24, v6
	v_mul_f32_e32 v4, v4, v7
	v_fmac_f32_e32 v25, v16, v29
	v_fmac_f32_e32 v5, v17, v9
	v_cvt_pk_bf16_f32 v4, v6, v4
	v_mul_f32_e32 v6, 0x3d372713, v25
	v_mul_f32_e32 v7, 0x3d372713, v5
	v_mul_f32_e32 v6, v25, v6
	v_mul_f32_e32 v7, v5, v7
	v_fma_f32 v6, v25, v6, v25
	v_fma_f32 v7, v5, v7, v5
	v_mul_f32_e32 v6, 0x3f4c422a, v6
	v_mul_f32_e32 v7, 0x3f4c422a, v7
	v_add_f32_e32 v6, v6, v6
	v_add_f32_e32 v7, v7, v7
	v_mul_f32_e32 v6, 0xbfb8aa3b, v6
	v_mul_f32_e32 v7, 0xbfb8aa3b, v7
	v_exp_f32_e32 v6, v6
	v_exp_f32_e32 v7, v7
	v_add_f32_e32 v6, 1.0, v6
	v_add_f32_e32 v7, 1.0, v7
	v_rcp_f32_e32 v6, v6
	v_rcp_f32_e32 v7, v7
	v_mul_f32_e32 v6, v25, v6
	v_mul_f32_e32 v5, v5, v7
	v_cvt_pk_bf16_f32 v5, v6, v5
	ds_read_b128 v[18:21], v246 offset:144
	ds_read_b128 v[22:25], v246 offset:128
	s_waitcnt vmcnt(22) lgkmcnt(0)
; __device__ __forceinline__ unsigned cvt_pk_bf16(float lo, float hi) { unsigned r; asm volatile("v_cvt_pk_bf16_f32 %0, %1, %2" : "=v"(r) : "v"(lo), "v"(hi)); return r; }
; __device__ __forceinline__ float gelu_tanh(float x) { const float u = 0.7978845608028654f * (x + 0.044715f * x * x * x); return x * sigm(2.f * u); }
; #define UNPK8(VV_, XX_) float XX_[8] = {bflo((VV_).x), bfhi((VV_).x), bflo((VV_).y), bfhi((VV_).y), bflo((VV_).z), bfhi((VV_).z), bflo((VV_).w), bfhi((VV_).w)}
; __device__ __forceinline__ void glu_task(int t, int l, const float* s5d, const bf16_t* P, const bf16_t* YB, const bf16_t* WGLU, bf16_t* Z1, int fr, int fq) {
;     ...
;     for (int tb = 0; tb < 2; ++tb) { const size_t row = row0 + tb * 16;
; #pragma unroll
;         for (int ks = 0; ks < 8; ++ks) { const int k0 = ks * 32 + fq * 8; const u32x4 yw = ld8(YB + row * 256 + k0), uw = ld8(P + row * INP + OFF_S5 + k0);
;             const f32x4 d0 = *(const f32x4*)(s5d + l * 256 + k0), d1 = *(const f32x4*)(s5d + l * 256 + k0 + 4); UNPK8(yw, y); UNPK8(uw, u); u32x4 o;
;             o.x = cvt_pk_bf16(gelu_tanh(y[0] + d0[0] * u[0]), gelu_tanh(y[1] + d0[1] * u[1])); o.y = cvt_pk_bf16(gelu_tanh(y[2] + d0[2] * u[2]), gelu_tanh(y[3] + d0[3] * u[3]));
;             o.z = cvt_pk_bf16(gelu_tanh(y[4] + d1[0] * u[4]), gelu_tanh(y[5] + d1[1] * u[5])); o.w = cvt_pk_bf16(gelu_tanh(y[6] + d1[2] * u[6]), gelu_tanh(y[7] + d1[3] * u[7]));
;             bfr[tb][ks] = asfrag(o); } }
	v_mov_b32_e32 v6, v106
	v_mov_b32_e32 v7, v107
	v_mov_b32_e32 v8, v108
	v_mov_b32_e32 v9, v109
	v_mov_b32_e32 v14, v110
	v_mov_b32_e32 v15, v111
	v_mov_b32_e32 v16, v112
	v_mov_b32_e32 v17, v113
	global_load_dwordx4 v[106:109], v[66:67], off offset:320
	global_load_dwordx4 v[110:113], v[68:69], off offset:640
	v_lshlrev_b32_e32 v26, 16, v6
	v_and_b32_e32 v6, 0xffff0000, v6
	v_lshlrev_b32_e32 v30, 16, v14
	v_and_b32_e32 v14, 0xffff0000, v14
	v_fmac_f32_e32 v6, v23, v14
	v_mul_f32_e32 v14, 0x3d372713, v6
	v_mul_f32_e32 v14, v6, v14
	v_fma_f32 v14, v6, v14, v6
	v_mul_f32_e32 v14, 0x3f4c422a, v14
	v_add_f32_e32 v14, v14, v14
	v_mul_f32_e32 v14, 0xbfb8aa3b, v14
	v_exp_f32_e32 v14, v14
	v_lshlrev_b32_e32 v27, 16, v7
	v_and_b32_e32 v7, 0xffff0000, v7
	v_lshlrev_b32_e32 v31, 16, v15
	v_add_f32_e32 v14, 1.0, v14
	v_rcp_f32_e32 v14, v14
	v_and_b32_e32 v15, 0xffff0000, v15
	v_fmac_f32_e32 v27, v24, v31
	v_fmac_f32_e32 v7, v25, v15
	v_fmac_f32_e32 v26, v22, v30
	v_mul_f32_e32 v6, v6, v14
	v_mul_f32_e32 v14, 0x3d372713, v27
	v_mul_f32_e32 v15, 0x3d372713, v7
	v_mul_f32_e32 v22, 0x3d372713, v26
	v_mul_f32_e32 v14, v27, v14
	v_mul_f32_e32 v15, v7, v15
	v_mul_f32_e32 v22, v26, v22
	v_fma_f32 v14, v27, v14, v27
	v_fma_f32 v15, v7, v15, v7
	v_fma_f32 v22, v26, v22, v26
	v_mul_f32_e32 v14, 0x3f4c422a, v14
	v_mul_f32_e32 v15, 0x3f4c422a, v15
	v_mul_f32_e32 v22, 0x3f4c422a, v22
	v_add_f32_e32 v14, v14, v14
	v_add_f32_e32 v15, v15, v15
	v_add_f32_e32 v22, v22, v22
	v_mul_f32_e32 v14, 0xbfb8aa3b, v14
	v_mul_f32_e32 v15, 0xbfb8aa3b, v15
	v_mul_f32_e32 v22, 0xbfb8aa3b, v22
	v_exp_f32_e32 v14, v14
	v_exp_f32_e32 v15, v15
	v_exp_f32_e32 v22, v22
	v_lshlrev_b32_e32 v28, 16, v8
	v_add_f32_e32 v14, 1.0, v14
	v_add_f32_e32 v15, 1.0, v15
	v_add_f32_e32 v22, 1.0, v22
	v_rcp_f32_e32 v14, v14
	v_rcp_f32_e32 v15, v15
	v_rcp_f32_e32 v22, v22
	v_and_b32_e32 v8, 0xffff0000, v8
	v_lshlrev_b32_e32 v32, 16, v16
	v_and_b32_e32 v16, 0xffff0000, v16
	v_mul_f32_e32 v14, v27, v14
	v_mul_f32_e32 v7, v7, v15
	v_fmac_f32_e32 v28, v18, v32
	v_fmac_f32_e32 v8, v19, v16
	v_mul_f32_e32 v22, v26, v22
	v_cvt_pk_bf16_f32 v6, v22, v6
	v_cvt_pk_bf16_f32 v7, v14, v7
	v_mul_f32_e32 v14, 0x3d372713, v28
	v_mul_f32_e32 v15, 0x3d372713, v8
	v_mul_f32_e32 v14, v28, v14
	v_mul_f32_e32 v15, v8, v15
	v_fma_f32 v14, v28, v14, v28
	v_fma_f32 v15, v8, v15, v8
	v_mul_f32_e32 v14, 0x3f4c422a, v14
	v_mul_f32_e32 v15, 0x3f4c422a, v15
	v_add_f32_e32 v14, v14, v14
	v_add_f32_e32 v15, v15, v15
	v_mul_f32_e32 v14, 0xbfb8aa3b, v14
	v_mul_f32_e32 v15, 0xbfb8aa3b, v15
	v_exp_f32_e32 v14, v14
	v_exp_f32_e32 v15, v15
	v_lshlrev_b32_e32 v29, 16, v9
	v_and_b32_e32 v9, 0xffff0000, v9
	v_add_f32_e32 v14, 1.0, v14
	v_add_f32_e32 v15, 1.0, v15
	v_rcp_f32_e32 v14, v14
	v_rcp_f32_e32 v15, v15
	v_lshlrev_b32_e32 v33, 16, v17
	v_and_b32_e32 v17, 0xffff0000, v17
	v_mul_f32_e32 v14, v28, v14
	v_mul_f32_e32 v8, v8, v15
	v_fmac_f32_e32 v29, v20, v33
	v_fmac_f32_e32 v9, v21, v17
	v_cvt_pk_bf16_f32 v8, v14, v8
	v_mul_f32_e32 v14, 0x3d372713, v29
	v_mul_f32_e32 v15, 0x3d372713, v9
	v_mul_f32_e32 v14, v29, v14
	v_mul_f32_e32 v15, v9, v15
	v_fma_f32 v14, v29, v14, v29
	v_fma_f32 v15, v9, v15, v9
	v_mul_f32_e32 v14, 0x3f4c422a, v14
	v_mul_f32_e32 v15, 0x3f4c422a, v15
	v_add_f32_e32 v14, v14, v14
	v_add_f32_e32 v15, v15, v15
	v_mul_f32_e32 v14, 0xbfb8aa3b, v14
	v_mul_f32_e32 v15, 0xbfb8aa3b, v15
	v_exp_f32_e32 v14, v14
	v_exp_f32_e32 v15, v15
	v_add_f32_e32 v14, 1.0, v14
	v_add_f32_e32 v15, 1.0, v15
	v_rcp_f32_e32 v14, v14
	v_rcp_f32_e32 v15, v15
	v_mul_f32_e32 v14, v29, v14
	v_mul_f32_e32 v9, v9, v15
	v_cvt_pk_bf16_f32 v9, v14, v9
	ds_read_b128 v[22:25], v246 offset:272
	ds_read_b128 v[26:29], v246 offset:256
	s_waitcnt vmcnt(22) lgkmcnt(0)
	v_mov_b32_e32 v14, v118
	v_mov_b32_e32 v15, v119
	v_mov_b32_e32 v16, v120
	v_mov_b32_e32 v17, v121
	v_mov_b32_e32 v18, v122
	v_mov_b32_e32 v19, v123
	v_mov_b32_e32 v20, v124
	v_mov_b32_e32 v21, v125
	global_load_dwordx4 v[118:121], v[66:67], off offset:384
	global_load_dwordx4 v[122:125], v[68:69], off offset:704
	v_lshlrev_b32_e32 v30, 16, v14
	v_and_b32_e32 v14, 0xffff0000, v14
	v_lshlrev_b32_e32 v38, 16, v18
	v_and_b32_e32 v18, 0xffff0000, v18
	v_fmac_f32_e32 v14, v27, v18
	v_mul_f32_e32 v18, 0x3d372713, v14
	v_mul_f32_e32 v18, v14, v18
	v_fma_f32 v18, v14, v18, v14
	v_mul_f32_e32 v18, 0x3f4c422a, v18
	v_add_f32_e32 v18, v18, v18
	v_mul_f32_e32 v18, 0xbfb8aa3b, v18
	v_exp_f32_e32 v18, v18
	v_lshlrev_b32_e32 v31, 16, v15
	v_and_b32_e32 v15, 0xffff0000, v15
	v_lshlrev_b32_e32 v39, 16, v19
	v_add_f32_e32 v18, 1.0, v18
	v_rcp_f32_e32 v18, v18
	v_and_b32_e32 v19, 0xffff0000, v19
	v_fmac_f32_e32 v31, v28, v39
	v_fmac_f32_e32 v15, v29, v19
	v_fmac_f32_e32 v30, v26, v38
	v_mul_f32_e32 v14, v14, v18
	v_mul_f32_e32 v18, 0x3d372713, v31
	v_mul_f32_e32 v19, 0x3d372713, v15
	v_mul_f32_e32 v26, 0x3d372713, v30
	v_mul_f32_e32 v18, v31, v18
	v_mul_f32_e32 v19, v15, v19
	v_mul_f32_e32 v26, v30, v26
	v_fma_f32 v18, v31, v18, v31
	v_fma_f32 v19, v15, v19, v15
	v_fma_f32 v26, v30, v26, v30
	v_mul_f32_e32 v18, 0x3f4c422a, v18
	v_mul_f32_e32 v19, 0x3f4c422a, v19
	v_mul_f32_e32 v26, 0x3f4c422a, v26
	v_add_f32_e32 v18, v18, v18
	v_add_f32_e32 v19, v19, v19
	v_add_f32_e32 v26, v26, v26
	v_mul_f32_e32 v18, 0xbfb8aa3b, v18
	v_mul_f32_e32 v19, 0xbfb8aa3b, v19
	v_mul_f32_e32 v26, 0xbfb8aa3b, v26
	v_exp_f32_e32 v18, v18
	v_exp_f32_e32 v19, v19
	v_exp_f32_e32 v26, v26
	v_lshlrev_b32_e32 v32, 16, v16
	v_add_f32_e32 v18, 1.0, v18
	v_add_f32_e32 v19, 1.0, v19
	v_add_f32_e32 v26, 1.0, v26
	v_rcp_f32_e32 v18, v18
	v_rcp_f32_e32 v19, v19
	v_rcp_f32_e32 v26, v26
	v_and_b32_e32 v16, 0xffff0000, v16
	v_lshlrev_b32_e32 v40, 16, v20
; __device__ __forceinline__ unsigned cvt_pk_bf16(float lo, float hi) { unsigned r; asm volatile("v_cvt_pk_bf16_f32 %0, %1, %2" : "=v"(r) : "v"(lo), "v"(hi)); return r; }
; __device__ __forceinline__ float gelu_tanh(float x) { const float u = 0.7978845608028654f * (x + 0.044715f * x * x * x); return x * sigm(2.f * u); }
; #define UNPK8(VV_, XX_) float XX_[8] = {bflo((VV_).x), bfhi((VV_).x), bflo((VV_).y), bfhi((VV_).y), bflo((VV_).z), bfhi((VV_).z), bflo((VV_).w), bfhi((VV_).w)}
; __device__ __forceinline__ void glu_task(int t, int l, const float* s5d, const bf16_t* P, const bf16_t* YB, const bf16_t* WGLU, bf16_t* Z1, int fr, int fq) {
;     ...
;     for (int tb = 0; tb < 2; ++tb) { const size_t row = row0 + tb * 16;
; #pragma unroll
;         for (int ks = 0; ks < 8; ++ks) { const int k0 = ks * 32 + fq * 8; const u32x4 yw = ld8(YB + row * 256 + k0), uw = ld8(P + row * INP + OFF_S5 + k0);
;             const f32x4 d0 = *(const f32x4*)(s5d + l * 256 + k0), d1 = *(const f32x4*)(s5d + l * 256 + k0 + 4); UNPK8(yw, y); UNPK8(uw, u); u32x4 o;
;             o.x = cvt_pk_bf16(gelu_tanh(y[0] + d0[0] * u[0]), gelu_tanh(y[1] + d0[1] * u[1])); o.y = cvt_pk_bf16(gelu_tanh(y[2] + d0[2] * u[2]), gelu_tanh(y[3] + d0[3] * u[3]));
;             o.z = cvt_pk_bf16(gelu_tanh(y[4] + d1[0] * u[4]), gelu_tanh(y[5] + d1[1] * u[5])); o.w = cvt_pk_bf16(gelu_tanh(y[6] + d1[2] * u[6]), gelu_tanh(y[7] + d1[3] * u[7]));
;             bfr[tb][ks] = asfrag(o); } }
	v_and_b32_e32 v20, 0xffff0000, v20
	v_mul_f32_e32 v18, v31, v18
	v_mul_f32_e32 v15, v15, v19
	v_fmac_f32_e32 v32, v22, v40
	v_fmac_f32_e32 v16, v23, v20
	v_mul_f32_e32 v26, v30, v26
	v_cvt_pk_bf16_f32 v14, v26, v14
	v_cvt_pk_bf16_f32 v15, v18, v15
	v_mul_f32_e32 v18, 0x3d372713, v32
	v_mul_f32_e32 v19, 0x3d372713, v16
	v_mul_f32_e32 v18, v32, v18
	v_mul_f32_e32 v19, v16, v19
	v_fma_f32 v18, v32, v18, v32
	v_fma_f32 v19, v16, v19, v16
	v_mul_f32_e32 v18, 0x3f4c422a, v18
	v_mul_f32_e32 v19, 0x3f4c422a, v19
	v_add_f32_e32 v18, v18, v18
	v_add_f32_e32 v19, v19, v19
	v_mul_f32_e32 v18, 0xbfb8aa3b, v18
	v_mul_f32_e32 v19, 0xbfb8aa3b, v19
	v_exp_f32_e32 v18, v18
	v_exp_f32_e32 v19, v19
	v_lshlrev_b32_e32 v33, 16, v17
	v_and_b32_e32 v17, 0xffff0000, v17
	v_add_f32_e32 v18, 1.0, v18
	v_add_f32_e32 v19, 1.0, v19
	v_rcp_f32_e32 v18, v18
	v_rcp_f32_e32 v19, v19
	v_lshlrev_b32_e32 v41, 16, v21
	v_and_b32_e32 v21, 0xffff0000, v21
	v_mul_f32_e32 v18, v32, v18
	v_mul_f32_e32 v16, v16, v19
	v_fmac_f32_e32 v33, v24, v41
	v_fmac_f32_e32 v17, v25, v21
	v_cvt_pk_bf16_f32 v16, v18, v16
	v_mul_f32_e32 v18, 0x3d372713, v33
	v_mul_f32_e32 v19, 0x3d372713, v17
	v_mul_f32_e32 v18, v33, v18
	v_mul_f32_e32 v19, v17, v19
	v_fma_f32 v18, v33, v18, v33
	v_fma_f32 v19, v17, v19, v17
	v_mul_f32_e32 v18, 0x3f4c422a, v18
	v_mul_f32_e32 v19, 0x3f4c422a, v19
	v_add_f32_e32 v18, v18, v18
	v_add_f32_e32 v19, v19, v19
	v_mul_f32_e32 v18, 0xbfb8aa3b, v18
	v_mul_f32_e32 v19, 0xbfb8aa3b, v19
	v_exp_f32_e32 v18, v18
	v_exp_f32_e32 v19, v19
	v_add_f32_e32 v18, 1.0, v18
	v_add_f32_e32 v19, 1.0, v19
	v_rcp_f32_e32 v18, v18
	v_rcp_f32_e32 v19, v19
	v_mul_f32_e32 v18, v33, v18
	v_mul_f32_e32 v17, v17, v19
	v_cvt_pk_bf16_f32 v17, v18, v17
	ds_read_b128 v[26:29], v246 offset:400
	ds_read_b128 v[30:33], v246 offset:384
	s_waitcnt vmcnt(22) lgkmcnt(0)
	v_mov_b32_e32 v18, v126
	v_mov_b32_e32 v19, v127
	v_mov_b32_e32 v20, v128
	v_mov_b32_e32 v21, v129
	v_mov_b32_e32 v22, v130
	v_mov_b32_e32 v23, v131
	v_mov_b32_e32 v24, v132
	v_mov_b32_e32 v25, v133
	global_load_dwordx4 v[126:129], v[66:67], off offset:448
	global_load_dwordx4 v[130:133], v[68:69], off offset:768
	v_lshlrev_b32_e32 v38, 16, v18
	v_and_b32_e32 v18, 0xffff0000, v18
	v_lshlrev_b32_e32 v42, 16, v22
	v_and_b32_e32 v22, 0xffff0000, v22
	v_fmac_f32_e32 v18, v31, v22
	v_mul_f32_e32 v22, 0x3d372713, v18
	v_mul_f32_e32 v22, v18, v22
	v_fma_f32 v22, v18, v22, v18
	v_mul_f32_e32 v22, 0x3f4c422a, v22
	v_add_f32_e32 v22, v22, v22
	v_mul_f32_e32 v22, 0xbfb8aa3b, v22
	v_exp_f32_e32 v22, v22
	v_lshlrev_b32_e32 v39, 16, v19
	v_and_b32_e32 v19, 0xffff0000, v19
	v_lshlrev_b32_e32 v43, 16, v23
	v_add_f32_e32 v22, 1.0, v22
	v_rcp_f32_e32 v22, v22
	v_and_b32_e32 v23, 0xffff0000, v23
	v_fmac_f32_e32 v39, v32, v43
	v_fmac_f32_e32 v19, v33, v23
	v_fmac_f32_e32 v38, v30, v42
	v_mul_f32_e32 v18, v18, v22
	v_mul_f32_e32 v22, 0x3d372713, v39
	v_mul_f32_e32 v23, 0x3d372713, v19
	v_mul_f32_e32 v30, 0x3d372713, v38
	v_mul_f32_e32 v22, v39, v22
	v_mul_f32_e32 v23, v19, v23
	v_mul_f32_e32 v30, v38, v30
	v_fma_f32 v22, v39, v22, v39
	v_fma_f32 v23, v19, v23, v19
	v_fma_f32 v30, v38, v30, v38
	v_mul_f32_e32 v22, 0x3f4c422a, v22
	v_mul_f32_e32 v23, 0x3f4c422a, v23
	v_mul_f32_e32 v30, 0x3f4c422a, v30
	v_add_f32_e32 v22, v22, v22
	v_add_f32_e32 v23, v23, v23
	v_add_f32_e32 v30, v30, v30
	v_mul_f32_e32 v22, 0xbfb8aa3b, v22
	v_mul_f32_e32 v23, 0xbfb8aa3b, v23
	v_mul_f32_e32 v30, 0xbfb8aa3b, v30
	v_exp_f32_e32 v22, v22
	v_exp_f32_e32 v23, v23
	v_exp_f32_e32 v30, v30
	v_lshlrev_b32_e32 v40, 16, v20
	v_add_f32_e32 v22, 1.0, v22
	v_add_f32_e32 v23, 1.0, v23
	v_add_f32_e32 v30, 1.0, v30
	v_rcp_f32_e32 v22, v22
	v_rcp_f32_e32 v23, v23
	v_rcp_f32_e32 v30, v30
	v_and_b32_e32 v20, 0xffff0000, v20
	v_lshlrev_b32_e32 v44, 16, v24
	v_and_b32_e32 v24, 0xffff0000, v24
	v_mul_f32_e32 v22, v39, v22
	v_mul_f32_e32 v19, v19, v23
	v_fmac_f32_e32 v40, v26, v44
	v_fmac_f32_e32 v20, v27, v24
	v_mul_f32_e32 v30, v38, v30
	v_cvt_pk_bf16_f32 v18, v30, v18
	v_cvt_pk_bf16_f32 v19, v22, v19
	v_mul_f32_e32 v22, 0x3d372713, v40
	v_mul_f32_e32 v23, 0x3d372713, v20
	v_mul_f32_e32 v22, v40, v22
	v_mul_f32_e32 v23, v20, v23
	v_fma_f32 v22, v40, v22, v40
	v_fma_f32 v23, v20, v23, v20
	v_mul_f32_e32 v22, 0x3f4c422a, v22
	v_mul_f32_e32 v23, 0x3f4c422a, v23
	v_add_f32_e32 v22, v22, v22
	v_add_f32_e32 v23, v23, v23
	v_mul_f32_e32 v22, 0xbfb8aa3b, v22
	v_mul_f32_e32 v23, 0xbfb8aa3b, v23
	v_exp_f32_e32 v22, v22
	v_exp_f32_e32 v23, v23
	v_lshlrev_b32_e32 v41, 16, v21
	v_and_b32_e32 v21, 0xffff0000, v21
	v_add_f32_e32 v22, 1.0, v22
	v_add_f32_e32 v23, 1.0, v23
	v_rcp_f32_e32 v22, v22
	v_rcp_f32_e32 v23, v23
	v_lshlrev_b32_e32 v45, 16, v25
	v_and_b32_e32 v25, 0xffff0000, v25
	v_mul_f32_e32 v22, v40, v22
	v_mul_f32_e32 v20, v20, v23
	v_fmac_f32_e32 v41, v28, v45
	v_fmac_f32_e32 v21, v29, v25
	v_cvt_pk_bf16_f32 v20, v22, v20
	v_mul_f32_e32 v22, 0x3d372713, v41
	v_mul_f32_e32 v23, 0x3d372713, v21
	v_mul_f32_e32 v22, v41, v22
	v_mul_f32_e32 v23, v21, v23
	v_fma_f32 v22, v41, v22, v41
	v_fma_f32 v23, v21, v23, v21
	v_mul_f32_e32 v22, 0x3f4c422a, v22
	v_mul_f32_e32 v23, 0x3f4c422a, v23
	v_add_f32_e32 v22, v22, v22
	v_add_f32_e32 v23, v23, v23
	v_mul_f32_e32 v22, 0xbfb8aa3b, v22
	v_mul_f32_e32 v23, 0xbfb8aa3b, v23
	v_exp_f32_e32 v22, v22
	v_exp_f32_e32 v23, v23
	v_add_f32_e32 v22, 1.0, v22
	v_add_f32_e32 v23, 1.0, v23
	v_rcp_f32_e32 v22, v22
	v_rcp_f32_e32 v23, v23
	v_mul_f32_e32 v22, v41, v22
	v_mul_f32_e32 v21, v21, v23
	v_cvt_pk_bf16_f32 v21, v22, v21
	ds_read_b128 v[30:33], v246 offset:528
	ds_read_b128 v[38:41], v246 offset:512
	s_waitcnt vmcnt(22) lgkmcnt(0)
; __device__ __forceinline__ unsigned cvt_pk_bf16(float lo, float hi) { unsigned r; asm volatile("v_cvt_pk_bf16_f32 %0, %1, %2" : "=v"(r) : "v"(lo), "v"(hi)); return r; }
; __device__ __forceinline__ float gelu_tanh(float x) { const float u = 0.7978845608028654f * (x + 0.044715f * x * x * x); return x * sigm(2.f * u); }
; #define UNPK8(VV_, XX_) float XX_[8] = {bflo((VV_).x), bfhi((VV_).x), bflo((VV_).y), bfhi((VV_).y), bflo((VV_).z), bfhi((VV_).z), bflo((VV_).w), bfhi((VV_).w)}
; __device__ __forceinline__ void glu_task(int t, int l, const float* s5d, const bf16_t* P, const bf16_t* YB, const bf16_t* WGLU, bf16_t* Z1, int fr, int fq) {
;     ...
;     for (int tb = 0; tb < 2; ++tb) { const size_t row = row0 + tb * 16;
; #pragma unroll
;         for (int ks = 0; ks < 8; ++ks) { const int k0 = ks * 32 + fq * 8; const u32x4 yw = ld8(YB + row * 256 + k0), uw = ld8(P + row * INP + OFF_S5 + k0);
;             const f32x4 d0 = *(const f32x4*)(s5d + l * 256 + k0), d1 = *(const f32x4*)(s5d + l * 256 + k0 + 4); UNPK8(yw, y); UNPK8(uw, u); u32x4 o;
;             o.x = cvt_pk_bf16(gelu_tanh(y[0] + d0[0] * u[0]), gelu_tanh(y[1] + d0[1] * u[1])); o.y = cvt_pk_bf16(gelu_tanh(y[2] + d0[2] * u[2]), gelu_tanh(y[3] + d0[3] * u[3]));
;             o.z = cvt_pk_bf16(gelu_tanh(y[4] + d1[0] * u[4]), gelu_tanh(y[5] + d1[1] * u[5])); o.w = cvt_pk_bf16(gelu_tanh(y[6] + d1[2] * u[6]), gelu_tanh(y[7] + d1[3] * u[7]));
;             bfr[tb][ks] = asfrag(o); } }
	v_mov_b32_e32 v22, v140
	v_mov_b32_e32 v23, v141
	v_mov_b32_e32 v24, v142
	v_mov_b32_e32 v25, v143
	v_mov_b32_e32 v26, v144
	v_mov_b32_e32 v27, v145
	v_mov_b32_e32 v28, v146
	v_mov_b32_e32 v29, v147
	v_lshlrev_b32_e32 v42, 16, v22
	v_and_b32_e32 v22, 0xffff0000, v22
	v_lshlrev_b32_e32 v46, 16, v26
	v_and_b32_e32 v26, 0xffff0000, v26
	v_fmac_f32_e32 v22, v39, v26
	v_mul_f32_e32 v26, 0x3d372713, v22
	v_mul_f32_e32 v26, v22, v26
	v_fma_f32 v26, v22, v26, v22
	v_mul_f32_e32 v26, 0x3f4c422a, v26
	v_add_f32_e32 v26, v26, v26
	v_mul_f32_e32 v26, 0xbfb8aa3b, v26
	v_exp_f32_e32 v26, v26
	v_lshlrev_b32_e32 v43, 16, v23
	v_and_b32_e32 v23, 0xffff0000, v23
	v_lshlrev_b32_e32 v47, 16, v27
	v_add_f32_e32 v26, 1.0, v26
	v_rcp_f32_e32 v26, v26
	v_and_b32_e32 v27, 0xffff0000, v27
	v_fmac_f32_e32 v43, v40, v47
	v_fmac_f32_e32 v23, v41, v27
	v_fmac_f32_e32 v42, v38, v46
	v_mul_f32_e32 v22, v22, v26
	v_mul_f32_e32 v26, 0x3d372713, v43
	v_mul_f32_e32 v27, 0x3d372713, v23
	v_mul_f32_e32 v38, 0x3d372713, v42
	v_mul_f32_e32 v26, v43, v26
	v_mul_f32_e32 v27, v23, v27
	v_mul_f32_e32 v38, v42, v38
	v_fma_f32 v26, v43, v26, v43
	v_fma_f32 v27, v23, v27, v23
	v_fma_f32 v38, v42, v38, v42
	v_mul_f32_e32 v26, 0x3f4c422a, v26
	v_mul_f32_e32 v27, 0x3f4c422a, v27
	v_mul_f32_e32 v38, 0x3f4c422a, v38
	v_add_f32_e32 v26, v26, v26
	v_add_f32_e32 v27, v27, v27
	v_add_f32_e32 v38, v38, v38
	v_mul_f32_e32 v26, 0xbfb8aa3b, v26
	v_mul_f32_e32 v27, 0xbfb8aa3b, v27
	v_mul_f32_e32 v38, 0xbfb8aa3b, v38
	v_exp_f32_e32 v26, v26
	v_exp_f32_e32 v27, v27
	v_exp_f32_e32 v38, v38
	v_lshlrev_b32_e32 v44, 16, v24
	v_add_f32_e32 v26, 1.0, v26
	v_add_f32_e32 v27, 1.0, v27
	v_add_f32_e32 v38, 1.0, v38
	v_rcp_f32_e32 v26, v26
	v_rcp_f32_e32 v27, v27
	v_rcp_f32_e32 v38, v38
	v_and_b32_e32 v24, 0xffff0000, v24
	v_lshlrev_b32_e32 v48, 16, v28
	v_and_b32_e32 v28, 0xffff0000, v28
	v_mul_f32_e32 v26, v43, v26
	v_mul_f32_e32 v23, v23, v27
	v_fmac_f32_e32 v44, v30, v48
	v_fmac_f32_e32 v24, v31, v28
	v_mul_f32_e32 v38, v42, v38
	v_cvt_pk_bf16_f32 v22, v38, v22
	v_cvt_pk_bf16_f32 v23, v26, v23
	v_mul_f32_e32 v26, 0x3d372713, v44
	v_mul_f32_e32 v27, 0x3d372713, v24
	v_mul_f32_e32 v26, v44, v26
	v_mul_f32_e32 v27, v24, v27
	v_fma_f32 v26, v44, v26, v44
	v_fma_f32 v27, v24, v27, v24
	v_mul_f32_e32 v26, 0x3f4c422a, v26
	v_mul_f32_e32 v27, 0x3f4c422a, v27
	v_add_f32_e32 v26, v26, v26
	v_add_f32_e32 v27, v27, v27
	v_mul_f32_e32 v26, 0xbfb8aa3b, v26
	v_mul_f32_e32 v27, 0xbfb8aa3b, v27
	v_exp_f32_e32 v26, v26
	v_exp_f32_e32 v27, v27
	v_lshlrev_b32_e32 v45, 16, v25
	v_and_b32_e32 v25, 0xffff0000, v25
	v_add_f32_e32 v26, 1.0, v26
	v_add_f32_e32 v27, 1.0, v27
	v_rcp_f32_e32 v26, v26
	v_rcp_f32_e32 v27, v27
	v_lshlrev_b32_e32 v49, 16, v29
	v_and_b32_e32 v29, 0xffff0000, v29
	v_mul_f32_e32 v26, v44, v26
	v_mul_f32_e32 v24, v24, v27
	v_fmac_f32_e32 v45, v32, v49
	v_fmac_f32_e32 v25, v33, v29
	v_cvt_pk_bf16_f32 v24, v26, v24
	v_mul_f32_e32 v26, 0x3d372713, v45
	v_mul_f32_e32 v27, 0x3d372713, v25
	v_mul_f32_e32 v26, v45, v26
	v_mul_f32_e32 v27, v25, v27
	v_fma_f32 v26, v45, v26, v45
	v_fma_f32 v27, v25, v27, v25
	v_mul_f32_e32 v26, 0x3f4c422a, v26
	v_mul_f32_e32 v27, 0x3f4c422a, v27
	v_add_f32_e32 v26, v26, v26
	v_add_f32_e32 v27, v27, v27
	v_mul_f32_e32 v26, 0xbfb8aa3b, v26
	v_mul_f32_e32 v27, 0xbfb8aa3b, v27
	v_exp_f32_e32 v26, v26
	v_exp_f32_e32 v27, v27
	v_add_f32_e32 v26, 1.0, v26
	v_add_f32_e32 v27, 1.0, v27
	v_rcp_f32_e32 v26, v26
	v_rcp_f32_e32 v27, v27
	v_mul_f32_e32 v26, v45, v26
	v_mul_f32_e32 v25, v25, v27
	v_cvt_pk_bf16_f32 v25, v26, v25
	ds_read_b128 v[38:41], v246 offset:656
	ds_read_b128 v[42:45], v246 offset:640
	s_waitcnt vmcnt(20) lgkmcnt(0)
	v_mov_b32_e32 v26, v160
	v_mov_b32_e32 v27, v161
	v_mov_b32_e32 v28, v162
	v_mov_b32_e32 v29, v163
	v_mov_b32_e32 v30, v164
	v_mov_b32_e32 v31, v165
	v_mov_b32_e32 v32, v166
	v_mov_b32_e32 v33, v167
	v_lshlrev_b32_e32 v46, 16, v26
	v_and_b32_e32 v26, 0xffff0000, v26
	v_lshlrev_b32_e32 v50, 16, v30
	v_and_b32_e32 v30, 0xffff0000, v30
	v_fmac_f32_e32 v26, v43, v30
	v_mul_f32_e32 v30, 0x3d372713, v26
	v_mul_f32_e32 v30, v26, v30
	v_fma_f32 v30, v26, v30, v26
	v_mul_f32_e32 v30, 0x3f4c422a, v30
	v_add_f32_e32 v30, v30, v30
	v_mul_f32_e32 v30, 0xbfb8aa3b, v30
	v_exp_f32_e32 v30, v30
	v_lshlrev_b32_e32 v47, 16, v27
	v_and_b32_e32 v27, 0xffff0000, v27
	v_lshlrev_b32_e32 v51, 16, v31
	v_add_f32_e32 v30, 1.0, v30
	v_rcp_f32_e32 v30, v30
	v_and_b32_e32 v31, 0xffff0000, v31
	v_fmac_f32_e32 v47, v44, v51
	v_fmac_f32_e32 v27, v45, v31
	v_fmac_f32_e32 v46, v42, v50
	v_mul_f32_e32 v26, v26, v30
	v_mul_f32_e32 v30, 0x3d372713, v47
	v_mul_f32_e32 v31, 0x3d372713, v27
	v_mul_f32_e32 v42, 0x3d372713, v46
	v_mul_f32_e32 v30, v47, v30
	v_mul_f32_e32 v31, v27, v31
	v_mul_f32_e32 v42, v46, v42
	v_fma_f32 v30, v47, v30, v47
	v_fma_f32 v31, v27, v31, v27
	v_fma_f32 v42, v46, v42, v46
	v_mul_f32_e32 v30, 0x3f4c422a, v30
	v_mul_f32_e32 v31, 0x3f4c422a, v31
	v_mul_f32_e32 v42, 0x3f4c422a, v42
	v_add_f32_e32 v30, v30, v30
	v_add_f32_e32 v31, v31, v31
	v_add_f32_e32 v42, v42, v42
	v_mul_f32_e32 v30, 0xbfb8aa3b, v30
	v_mul_f32_e32 v31, 0xbfb8aa3b, v31
	v_mul_f32_e32 v42, 0xbfb8aa3b, v42
	v_exp_f32_e32 v30, v30
	v_exp_f32_e32 v31, v31
	v_exp_f32_e32 v42, v42
	v_lshlrev_b32_e32 v48, 16, v28
	v_add_f32_e32 v30, 1.0, v30
	v_add_f32_e32 v31, 1.0, v31
	v_add_f32_e32 v42, 1.0, v42
	v_rcp_f32_e32 v30, v30
	v_rcp_f32_e32 v31, v31
	v_rcp_f32_e32 v42, v42
	v_and_b32_e32 v28, 0xffff0000, v28
	v_lshlrev_b32_e32 v52, 16, v32
	v_and_b32_e32 v32, 0xffff0000, v32
	v_mul_f32_e32 v30, v47, v30
	v_mul_f32_e32 v27, v27, v31
	v_fmac_f32_e32 v48, v38, v52
	v_fmac_f32_e32 v28, v39, v32
	v_mul_f32_e32 v42, v46, v42
; __device__ __forceinline__ unsigned cvt_pk_bf16(float lo, float hi) { unsigned r; asm volatile("v_cvt_pk_bf16_f32 %0, %1, %2" : "=v"(r) : "v"(lo), "v"(hi)); return r; }
; __device__ __forceinline__ float gelu_tanh(float x) { const float u = 0.7978845608028654f * (x + 0.044715f * x * x * x); return x * sigm(2.f * u); }
; #define UNPK8(VV_, XX_) float XX_[8] = {bflo((VV_).x), bfhi((VV_).x), bflo((VV_).y), bfhi((VV_).y), bflo((VV_).z), bfhi((VV_).z), bflo((VV_).w), bfhi((VV_).w)}
; __device__ __forceinline__ void glu_task(int t, int l, const float* s5d, const bf16_t* P, const bf16_t* YB, const bf16_t* WGLU, bf16_t* Z1, int fr, int fq) {
;     ...
;     for (int tb = 0; tb < 2; ++tb) { const size_t row = row0 + tb * 16;
; #pragma unroll
;         for (int ks = 0; ks < 8; ++ks) { const int k0 = ks * 32 + fq * 8; const u32x4 yw = ld8(YB + row * 256 + k0), uw = ld8(P + row * INP + OFF_S5 + k0);
;             const f32x4 d0 = *(const f32x4*)(s5d + l * 256 + k0), d1 = *(const f32x4*)(s5d + l * 256 + k0 + 4); UNPK8(yw, y); UNPK8(uw, u); u32x4 o;
;             o.x = cvt_pk_bf16(gelu_tanh(y[0] + d0[0] * u[0]), gelu_tanh(y[1] + d0[1] * u[1])); o.y = cvt_pk_bf16(gelu_tanh(y[2] + d0[2] * u[2]), gelu_tanh(y[3] + d0[3] * u[3]));
;             o.z = cvt_pk_bf16(gelu_tanh(y[4] + d1[0] * u[4]), gelu_tanh(y[5] + d1[1] * u[5])); o.w = cvt_pk_bf16(gelu_tanh(y[6] + d1[2] * u[6]), gelu_tanh(y[7] + d1[3] * u[7]));
;             bfr[tb][ks] = asfrag(o); } }
	v_cvt_pk_bf16_f32 v26, v42, v26
	v_cvt_pk_bf16_f32 v27, v30, v27
	v_mul_f32_e32 v30, 0x3d372713, v48
	v_mul_f32_e32 v31, 0x3d372713, v28
	v_mul_f32_e32 v30, v48, v30
	v_mul_f32_e32 v31, v28, v31
	v_fma_f32 v30, v48, v30, v48
	v_fma_f32 v31, v28, v31, v28
	v_mul_f32_e32 v30, 0x3f4c422a, v30
	v_mul_f32_e32 v31, 0x3f4c422a, v31
	v_add_f32_e32 v30, v30, v30
	v_add_f32_e32 v31, v31, v31
	v_mul_f32_e32 v30, 0xbfb8aa3b, v30
	v_mul_f32_e32 v31, 0xbfb8aa3b, v31
	v_exp_f32_e32 v30, v30
	v_exp_f32_e32 v31, v31
	v_lshlrev_b32_e32 v49, 16, v29
	v_and_b32_e32 v29, 0xffff0000, v29
	v_add_f32_e32 v30, 1.0, v30
	v_add_f32_e32 v31, 1.0, v31
	v_rcp_f32_e32 v30, v30
	v_rcp_f32_e32 v31, v31
	v_lshlrev_b32_e32 v53, 16, v33
	v_and_b32_e32 v33, 0xffff0000, v33
	v_mul_f32_e32 v30, v48, v30
	v_mul_f32_e32 v28, v28, v31
	v_fmac_f32_e32 v49, v40, v53
	v_fmac_f32_e32 v29, v41, v33
	v_cvt_pk_bf16_f32 v28, v30, v28
	v_mul_f32_e32 v30, 0x3d372713, v49
	v_mul_f32_e32 v31, 0x3d372713, v29
	v_mul_f32_e32 v30, v49, v30
	v_mul_f32_e32 v31, v29, v31
	v_fma_f32 v30, v49, v30, v49
	v_fma_f32 v31, v29, v31, v29
	v_mul_f32_e32 v30, 0x3f4c422a, v30
	v_mul_f32_e32 v31, 0x3f4c422a, v31
	v_add_f32_e32 v30, v30, v30
	v_add_f32_e32 v31, v31, v31
	v_mul_f32_e32 v30, 0xbfb8aa3b, v30
	v_mul_f32_e32 v31, 0xbfb8aa3b, v31
	v_exp_f32_e32 v30, v30
	v_exp_f32_e32 v31, v31
	v_add_f32_e32 v30, 1.0, v30
	v_add_f32_e32 v31, 1.0, v31
	v_rcp_f32_e32 v30, v30
	v_rcp_f32_e32 v31, v31
	v_mul_f32_e32 v30, v49, v30
	v_mul_f32_e32 v29, v29, v31
	v_cvt_pk_bf16_f32 v29, v30, v29
	ds_read_b128 v[42:45], v246 offset:784
	ds_read_b128 v[46:49], v246 offset:768
	s_waitcnt vmcnt(18) lgkmcnt(0)
	v_mov_b32_e32 v30, v180
	v_mov_b32_e32 v31, v181
	v_mov_b32_e32 v32, v182
	v_mov_b32_e32 v33, v183
	v_mov_b32_e32 v38, v184
	v_mov_b32_e32 v39, v185
	v_mov_b32_e32 v40, v186
	v_mov_b32_e32 v41, v187
	v_lshlrev_b32_e32 v50, 16, v30
	v_and_b32_e32 v30, 0xffff0000, v30
	v_lshlrev_b32_e32 v54, 16, v38
	v_and_b32_e32 v38, 0xffff0000, v38
	v_fmac_f32_e32 v30, v47, v38
	v_mul_f32_e32 v38, 0x3d372713, v30
	v_mul_f32_e32 v38, v30, v38
	v_fma_f32 v38, v30, v38, v30
	v_mul_f32_e32 v38, 0x3f4c422a, v38
	v_add_f32_e32 v38, v38, v38
	v_mul_f32_e32 v38, 0xbfb8aa3b, v38
	v_exp_f32_e32 v38, v38
	v_lshlrev_b32_e32 v51, 16, v31
	v_and_b32_e32 v31, 0xffff0000, v31
	v_lshlrev_b32_e32 v55, 16, v39
	v_add_f32_e32 v38, 1.0, v38
	v_rcp_f32_e32 v38, v38
	v_and_b32_e32 v39, 0xffff0000, v39
	v_fmac_f32_e32 v51, v48, v55
	v_fmac_f32_e32 v31, v49, v39
	v_fmac_f32_e32 v50, v46, v54
	v_mul_f32_e32 v30, v30, v38
	v_mul_f32_e32 v38, 0x3d372713, v51
	v_mul_f32_e32 v39, 0x3d372713, v31
	v_mul_f32_e32 v46, 0x3d372713, v50
	v_mul_f32_e32 v38, v51, v38
	v_mul_f32_e32 v39, v31, v39
	v_mul_f32_e32 v46, v50, v46
	v_fma_f32 v38, v51, v38, v51
	v_fma_f32 v39, v31, v39, v31
	v_fma_f32 v46, v50, v46, v50
	v_mul_f32_e32 v38, 0x3f4c422a, v38
	v_mul_f32_e32 v39, 0x3f4c422a, v39
	v_mul_f32_e32 v46, 0x3f4c422a, v46
	v_add_f32_e32 v38, v38, v38
	v_add_f32_e32 v39, v39, v39
	v_add_f32_e32 v46, v46, v46
	v_mul_f32_e32 v38, 0xbfb8aa3b, v38
	v_mul_f32_e32 v39, 0xbfb8aa3b, v39
	v_mul_f32_e32 v46, 0xbfb8aa3b, v46
	v_exp_f32_e32 v38, v38
	v_exp_f32_e32 v39, v39
	v_exp_f32_e32 v46, v46
	v_lshlrev_b32_e32 v52, 16, v32
	v_add_f32_e32 v38, 1.0, v38
	v_add_f32_e32 v39, 1.0, v39
	v_add_f32_e32 v46, 1.0, v46
	v_rcp_f32_e32 v38, v38
	v_rcp_f32_e32 v39, v39
	v_rcp_f32_e32 v46, v46
	v_and_b32_e32 v32, 0xffff0000, v32
	v_lshlrev_b32_e32 v56, 16, v40
	v_and_b32_e32 v40, 0xffff0000, v40
	v_mul_f32_e32 v38, v51, v38
	v_mul_f32_e32 v31, v31, v39
	v_fmac_f32_e32 v52, v42, v56
	v_fmac_f32_e32 v32, v43, v40
	v_mul_f32_e32 v46, v50, v46
	v_cvt_pk_bf16_f32 v30, v46, v30
	v_cvt_pk_bf16_f32 v31, v38, v31
	v_mul_f32_e32 v38, 0x3d372713, v52
	v_mul_f32_e32 v39, 0x3d372713, v32
	v_mul_f32_e32 v38, v52, v38
	v_mul_f32_e32 v39, v32, v39
	v_fma_f32 v38, v52, v38, v52
	v_fma_f32 v39, v32, v39, v32
	v_mul_f32_e32 v38, 0x3f4c422a, v38
	v_mul_f32_e32 v39, 0x3f4c422a, v39
	v_add_f32_e32 v38, v38, v38
	v_add_f32_e32 v39, v39, v39
	v_mul_f32_e32 v38, 0xbfb8aa3b, v38
	v_mul_f32_e32 v39, 0xbfb8aa3b, v39
	v_exp_f32_e32 v38, v38
	v_exp_f32_e32 v39, v39
	v_lshlrev_b32_e32 v53, 16, v33
	v_and_b32_e32 v33, 0xffff0000, v33
	v_add_f32_e32 v38, 1.0, v38
	v_add_f32_e32 v39, 1.0, v39
	v_rcp_f32_e32 v38, v38
	v_rcp_f32_e32 v39, v39
	v_lshlrev_b32_e32 v57, 16, v41
	v_and_b32_e32 v41, 0xffff0000, v41
	v_mul_f32_e32 v38, v52, v38
	v_mul_f32_e32 v32, v32, v39
	v_fmac_f32_e32 v53, v44, v57
	v_fmac_f32_e32 v33, v45, v41
	v_cvt_pk_bf16_f32 v32, v38, v32
	v_mul_f32_e32 v38, 0x3d372713, v53
	v_mul_f32_e32 v39, 0x3d372713, v33
	v_mul_f32_e32 v38, v53, v38
	v_mul_f32_e32 v39, v33, v39
	v_fma_f32 v38, v53, v38, v53
	v_fma_f32 v39, v33, v39, v33
	v_mul_f32_e32 v38, 0x3f4c422a, v38
	v_mul_f32_e32 v39, 0x3f4c422a, v39
	v_add_f32_e32 v38, v38, v38
	v_add_f32_e32 v39, v39, v39
	v_mul_f32_e32 v38, 0xbfb8aa3b, v38
	v_mul_f32_e32 v39, 0xbfb8aa3b, v39
	v_exp_f32_e32 v38, v38
	v_exp_f32_e32 v39, v39
	v_add_f32_e32 v38, 1.0, v38
	v_add_f32_e32 v39, 1.0, v39
	v_rcp_f32_e32 v38, v38
	v_rcp_f32_e32 v39, v39
	v_mul_f32_e32 v38, v53, v38
	v_mul_f32_e32 v33, v33, v39
	v_cvt_pk_bf16_f32 v33, v38, v33
	s_nop 0
	s_nop 0
	ds_read_b128 v[42:45], v246 offset:912
	ds_read_b128 v[46:49], v246 offset:896
	s_waitcnt vmcnt(16) lgkmcnt(0)
; __device__ __forceinline__ unsigned cvt_pk_bf16(float lo, float hi) { unsigned r; asm volatile("v_cvt_pk_bf16_f32 %0, %1, %2" : "=v"(r) : "v"(lo), "v"(hi)); return r; }
; __device__ __forceinline__ float gelu_tanh(float x) { const float u = 0.7978845608028654f * (x + 0.044715f * x * x * x); return x * sigm(2.f * u); }
; #define UNPK8(VV_, XX_) float XX_[8] = {bflo((VV_).x), bfhi((VV_).x), bflo((VV_).y), bfhi((VV_).y), bflo((VV_).z), bfhi((VV_).z), bflo((VV_).w), bfhi((VV_).w)}
; __device__ __forceinline__ void glu_task(int t, int l, const float* s5d, const bf16_t* P, const bf16_t* YB, const bf16_t* WGLU, bf16_t* Z1, int fr, int fq) {
;     ...
;     for (int tb = 0; tb < 2; ++tb) { const size_t row = row0 + tb * 16;
; #pragma unroll
;         for (int ks = 0; ks < 8; ++ks) { const int k0 = ks * 32 + fq * 8; const u32x4 yw = ld8(YB + row * 256 + k0), uw = ld8(P + row * INP + OFF_S5 + k0);
;             const f32x4 d0 = *(const f32x4*)(s5d + l * 256 + k0), d1 = *(const f32x4*)(s5d + l * 256 + k0 + 4); UNPK8(yw, y); UNPK8(uw, u); u32x4 o;
;             o.x = cvt_pk_bf16(gelu_tanh(y[0] + d0[0] * u[0]), gelu_tanh(y[1] + d0[1] * u[1])); o.y = cvt_pk_bf16(gelu_tanh(y[2] + d0[2] * u[2]), gelu_tanh(y[3] + d0[3] * u[3]));
;             o.z = cvt_pk_bf16(gelu_tanh(y[4] + d1[0] * u[4]), gelu_tanh(y[5] + d1[1] * u[5])); o.w = cvt_pk_bf16(gelu_tanh(y[6] + d1[2] * u[6]), gelu_tanh(y[7] + d1[3] * u[7]));
;             bfr[tb][ks] = asfrag(o); } }
	v_mov_b32_e32 v38, v214
	v_mov_b32_e32 v39, v215
	v_mov_b32_e32 v40, v216
	v_mov_b32_e32 v41, v217
	v_mov_b32_e32 v34, v218
	v_mov_b32_e32 v35, v219
	v_mov_b32_e32 v36, v220
	v_mov_b32_e32 v37, v221
	v_lshlrev_b32_e32 v50, 16, v38
	v_and_b32_e32 v38, 0xffff0000, v38
	v_lshlrev_b32_e32 v54, 16, v34
	v_and_b32_e32 v34, 0xffff0000, v34
	v_fmac_f32_e32 v38, v47, v34
	v_mul_f32_e32 v34, 0x3d372713, v38
	v_mul_f32_e32 v34, v38, v34
	v_fma_f32 v34, v38, v34, v38
	v_mul_f32_e32 v34, 0x3f4c422a, v34
	v_add_f32_e32 v34, v34, v34
	v_mul_f32_e32 v34, 0xbfb8aa3b, v34
	v_exp_f32_e32 v34, v34
	v_lshlrev_b32_e32 v51, 16, v39
	v_and_b32_e32 v39, 0xffff0000, v39
	v_lshlrev_b32_e32 v55, 16, v35
	v_add_f32_e32 v34, 1.0, v34
	v_rcp_f32_e32 v34, v34
	v_and_b32_e32 v35, 0xffff0000, v35
	v_fmac_f32_e32 v51, v48, v55
	v_fmac_f32_e32 v39, v49, v35
	v_fmac_f32_e32 v50, v46, v54
	v_mul_f32_e32 v34, v38, v34
	v_mul_f32_e32 v38, 0x3d372713, v51
	v_mul_f32_e32 v35, 0x3d372713, v39
	v_mul_f32_e32 v46, 0x3d372713, v50
	v_mul_f32_e32 v38, v51, v38
	v_mul_f32_e32 v35, v39, v35
	v_mul_f32_e32 v46, v50, v46
	v_fma_f32 v38, v51, v38, v51
	v_fma_f32 v35, v39, v35, v39
	v_fma_f32 v46, v50, v46, v50
	v_mul_f32_e32 v38, 0x3f4c422a, v38
	v_mul_f32_e32 v35, 0x3f4c422a, v35
	v_mul_f32_e32 v46, 0x3f4c422a, v46
	v_add_f32_e32 v38, v38, v38
	v_add_f32_e32 v35, v35, v35
	v_add_f32_e32 v46, v46, v46
	v_mul_f32_e32 v38, 0xbfb8aa3b, v38
	v_mul_f32_e32 v35, 0xbfb8aa3b, v35
	v_mul_f32_e32 v46, 0xbfb8aa3b, v46
	v_exp_f32_e32 v38, v38
	v_exp_f32_e32 v35, v35
	v_exp_f32_e32 v46, v46
	v_lshlrev_b32_e32 v52, 16, v40
	v_add_f32_e32 v38, 1.0, v38
	v_add_f32_e32 v35, 1.0, v35
	v_add_f32_e32 v46, 1.0, v46
	v_rcp_f32_e32 v38, v38
	v_rcp_f32_e32 v35, v35
	v_rcp_f32_e32 v46, v46
	v_and_b32_e32 v40, 0xffff0000, v40
	v_lshlrev_b32_e32 v56, 16, v36
	v_and_b32_e32 v36, 0xffff0000, v36
	v_mul_f32_e32 v38, v51, v38
	v_mul_f32_e32 v35, v39, v35
	v_fmac_f32_e32 v52, v42, v56
	v_fmac_f32_e32 v40, v43, v36
	v_mul_f32_e32 v46, v50, v46
	v_cvt_pk_bf16_f32 v34, v46, v34
	v_cvt_pk_bf16_f32 v35, v38, v35
	v_mul_f32_e32 v38, 0x3d372713, v52
	v_mul_f32_e32 v36, 0x3d372713, v40
	v_mul_f32_e32 v38, v52, v38
	v_mul_f32_e32 v36, v40, v36
	v_fma_f32 v38, v52, v38, v52
	v_fma_f32 v36, v40, v36, v40
	v_mul_f32_e32 v38, 0x3f4c422a, v38
	v_mul_f32_e32 v36, 0x3f4c422a, v36
	v_add_f32_e32 v38, v38, v38
	v_add_f32_e32 v36, v36, v36
	v_mul_f32_e32 v38, 0xbfb8aa3b, v38
	v_mul_f32_e32 v36, 0xbfb8aa3b, v36
	v_exp_f32_e32 v38, v38
	v_exp_f32_e32 v36, v36
	v_lshlrev_b32_e32 v53, 16, v41
	v_and_b32_e32 v41, 0xffff0000, v41
	v_add_f32_e32 v38, 1.0, v38
	v_add_f32_e32 v36, 1.0, v36
	v_rcp_f32_e32 v38, v38
	v_rcp_f32_e32 v36, v36
	v_lshlrev_b32_e32 v57, 16, v37
	v_and_b32_e32 v37, 0xffff0000, v37
	v_mul_f32_e32 v38, v52, v38
	v_mul_f32_e32 v36, v40, v36
	v_fmac_f32_e32 v53, v44, v57
	v_fmac_f32_e32 v41, v45, v37
	v_cvt_pk_bf16_f32 v36, v38, v36
	v_mul_f32_e32 v38, 0x3d372713, v53
	v_mul_f32_e32 v37, 0x3d372713, v41
	v_mul_f32_e32 v38, v53, v38
	v_mul_f32_e32 v37, v41, v37
	v_fma_f32 v38, v53, v38, v53
	v_fma_f32 v37, v41, v37, v41
	v_mul_f32_e32 v38, 0x3f4c422a, v38
	v_mul_f32_e32 v37, 0x3f4c422a, v37
	v_add_f32_e32 v38, v38, v38
	v_add_f32_e32 v37, v37, v37
	v_mul_f32_e32 v38, 0xbfb8aa3b, v38
	v_mul_f32_e32 v37, 0xbfb8aa3b, v37
	v_exp_f32_e32 v38, v38
	v_exp_f32_e32 v37, v37
	v_add_f32_e32 v38, 1.0, v38
	v_add_f32_e32 v37, 1.0, v37
	v_rcp_f32_e32 v38, v38
	v_rcp_f32_e32 v37, v37
	v_mul_f32_e32 v38, v53, v38
	v_mul_f32_e32 v37, v41, v37
	v_cvt_pk_bf16_f32 v37, v38, v37
	ds_read_b128 v[46:49], v246 offset:16
	ds_read_b128 v[50:53], v246
	s_waitcnt vmcnt(14) lgkmcnt(0)
	v_mov_b32_e32 v38, v222
	v_mov_b32_e32 v39, v223
	v_mov_b32_e32 v40, v224
	v_mov_b32_e32 v41, v225
	v_mov_b32_e32 v42, v226
	v_mov_b32_e32 v43, v227
	v_mov_b32_e32 v44, v228
	v_mov_b32_e32 v45, v229
	v_lshlrev_b32_e32 v58, 16, v42
	v_lshlrev_b32_e32 v54, 16, v38
	v_and_b32_e32 v38, 0xffff0000, v38
	v_and_b32_e32 v42, 0xffff0000, v42
	v_fmac_f32_e32 v38, v51, v42
	v_mul_f32_e32 v42, 0x3d372713, v38
	v_mul_f32_e32 v42, v38, v42
	v_fma_f32 v42, v38, v42, v38
	v_mul_f32_e32 v42, 0x3f4c422a, v42
	v_add_f32_e32 v42, v42, v42
	v_mul_f32_e32 v42, 0xbfb8aa3b, v42
	v_exp_f32_e32 v42, v42
	v_lshlrev_b32_e32 v55, 16, v39
	v_and_b32_e32 v39, 0xffff0000, v39
	v_lshlrev_b32_e32 v59, 16, v43
	v_add_f32_e32 v42, 1.0, v42
	v_rcp_f32_e32 v42, v42
	v_and_b32_e32 v43, 0xffff0000, v43
	v_fmac_f32_e32 v55, v52, v59
	v_fmac_f32_e32 v39, v53, v43
	v_fmac_f32_e32 v54, v50, v58
	v_mul_f32_e32 v38, v38, v42
	v_mul_f32_e32 v42, 0x3d372713, v55
	v_mul_f32_e32 v43, 0x3d372713, v39
	v_mul_f32_e32 v50, 0x3d372713, v54
	v_mul_f32_e32 v42, v55, v42
	v_mul_f32_e32 v43, v39, v43
	v_mul_f32_e32 v50, v54, v50
	v_fma_f32 v42, v55, v42, v55
	v_fma_f32 v43, v39, v43, v39
	v_fma_f32 v50, v54, v50, v54
	v_mul_f32_e32 v42, 0x3f4c422a, v42
	v_mul_f32_e32 v43, 0x3f4c422a, v43
	v_mul_f32_e32 v50, 0x3f4c422a, v50
	v_add_f32_e32 v42, v42, v42
	v_add_f32_e32 v43, v43, v43
	v_add_f32_e32 v50, v50, v50
	v_mul_f32_e32 v42, 0xbfb8aa3b, v42
	v_mul_f32_e32 v43, 0xbfb8aa3b, v43
	v_mul_f32_e32 v50, 0xbfb8aa3b, v50
	v_exp_f32_e32 v42, v42
	v_exp_f32_e32 v43, v43
	v_exp_f32_e32 v50, v50
	v_lshlrev_b32_e32 v56, 16, v40
	v_add_f32_e32 v42, 1.0, v42
	v_add_f32_e32 v43, 1.0, v43
	v_add_f32_e32 v50, 1.0, v50
	v_rcp_f32_e32 v42, v42
	v_rcp_f32_e32 v43, v43
	v_rcp_f32_e32 v50, v50
	v_and_b32_e32 v40, 0xffff0000, v40
	v_lshlrev_b32_e32 v60, 16, v44
	v_and_b32_e32 v44, 0xffff0000, v44
	v_mul_f32_e32 v42, v55, v42
	v_mul_f32_e32 v39, v39, v43
	v_fmac_f32_e32 v56, v46, v60
	v_fmac_f32_e32 v40, v47, v44
	v_mul_f32_e32 v50, v54, v50
; __device__ __forceinline__ unsigned cvt_pk_bf16(float lo, float hi) { unsigned r; asm volatile("v_cvt_pk_bf16_f32 %0, %1, %2" : "=v"(r) : "v"(lo), "v"(hi)); return r; }
; __device__ __forceinline__ float gelu_tanh(float x) { const float u = 0.7978845608028654f * (x + 0.044715f * x * x * x); return x * sigm(2.f * u); }
; #define UNPK8(VV_, XX_) float XX_[8] = {bflo((VV_).x), bfhi((VV_).x), bflo((VV_).y), bfhi((VV_).y), bflo((VV_).z), bfhi((VV_).z), bflo((VV_).w), bfhi((VV_).w)}
; __device__ __forceinline__ void glu_task(int t, int l, const float* s5d, const bf16_t* P, const bf16_t* YB, const bf16_t* WGLU, bf16_t* Z1, int fr, int fq) {
;     ...
;     for (int tb = 0; tb < 2; ++tb) { const size_t row = row0 + tb * 16;
; #pragma unroll
;         for (int ks = 0; ks < 8; ++ks) { const int k0 = ks * 32 + fq * 8; const u32x4 yw = ld8(YB + row * 256 + k0), uw = ld8(P + row * INP + OFF_S5 + k0);
;             const f32x4 d0 = *(const f32x4*)(s5d + l * 256 + k0), d1 = *(const f32x4*)(s5d + l * 256 + k0 + 4); UNPK8(yw, y); UNPK8(uw, u); u32x4 o;
;             o.x = cvt_pk_bf16(gelu_tanh(y[0] + d0[0] * u[0]), gelu_tanh(y[1] + d0[1] * u[1])); o.y = cvt_pk_bf16(gelu_tanh(y[2] + d0[2] * u[2]), gelu_tanh(y[3] + d0[3] * u[3]));
;             o.z = cvt_pk_bf16(gelu_tanh(y[4] + d1[0] * u[4]), gelu_tanh(y[5] + d1[1] * u[5])); o.w = cvt_pk_bf16(gelu_tanh(y[6] + d1[2] * u[6]), gelu_tanh(y[7] + d1[3] * u[7]));
;             bfr[tb][ks] = asfrag(o); } }
	v_cvt_pk_bf16_f32 v38, v50, v38
	v_cvt_pk_bf16_f32 v39, v42, v39
	v_mul_f32_e32 v42, 0x3d372713, v56
	v_mul_f32_e32 v43, 0x3d372713, v40
	v_mul_f32_e32 v42, v56, v42
	v_mul_f32_e32 v43, v40, v43
	v_fma_f32 v42, v56, v42, v56
	v_fma_f32 v43, v40, v43, v40
	v_mul_f32_e32 v42, 0x3f4c422a, v42
	v_mul_f32_e32 v43, 0x3f4c422a, v43
	v_add_f32_e32 v42, v42, v42
	v_add_f32_e32 v43, v43, v43
	v_mul_f32_e32 v42, 0xbfb8aa3b, v42
	v_mul_f32_e32 v43, 0xbfb8aa3b, v43
	v_exp_f32_e32 v42, v42
	v_exp_f32_e32 v43, v43
	v_lshlrev_b32_e32 v57, 16, v41
	v_and_b32_e32 v41, 0xffff0000, v41
	v_add_f32_e32 v42, 1.0, v42
	v_add_f32_e32 v43, 1.0, v43
	v_rcp_f32_e32 v42, v42
	v_rcp_f32_e32 v43, v43
	v_lshlrev_b32_e32 v61, 16, v45
	v_and_b32_e32 v45, 0xffff0000, v45
	v_mul_f32_e32 v42, v56, v42
	v_mul_f32_e32 v40, v40, v43
	v_fmac_f32_e32 v57, v48, v61
	v_fmac_f32_e32 v41, v49, v45
	v_cvt_pk_bf16_f32 v40, v42, v40
	v_mul_f32_e32 v42, 0x3d372713, v57
	v_mul_f32_e32 v43, 0x3d372713, v41
	v_mul_f32_e32 v42, v57, v42
	v_mul_f32_e32 v43, v41, v43
	v_fma_f32 v42, v57, v42, v57
	v_fma_f32 v43, v41, v43, v41
	v_mul_f32_e32 v42, 0x3f4c422a, v42
	v_mul_f32_e32 v43, 0x3f4c422a, v43
	v_add_f32_e32 v42, v42, v42
	v_add_f32_e32 v43, v43, v43
	v_mul_f32_e32 v42, 0xbfb8aa3b, v42
	v_mul_f32_e32 v43, 0xbfb8aa3b, v43
	v_exp_f32_e32 v42, v42
	v_exp_f32_e32 v43, v43
	v_add_f32_e32 v42, 1.0, v42
	v_add_f32_e32 v43, 1.0, v43
	v_rcp_f32_e32 v42, v42
	v_rcp_f32_e32 v43, v43
	v_mul_f32_e32 v42, v57, v42
	v_mul_f32_e32 v41, v41, v43
	v_cvt_pk_bf16_f32 v41, v42, v41
	ds_read_b128 v[50:53], v246 offset:144
	ds_read_b128 v[54:57], v246 offset:128
	s_waitcnt vmcnt(12) lgkmcnt(0)
	v_mov_b32_e32 v42, v230
	v_mov_b32_e32 v43, v231
	v_mov_b32_e32 v44, v232
	v_mov_b32_e32 v45, v233
	v_mov_b32_e32 v46, v234
	v_mov_b32_e32 v47, v235
	v_mov_b32_e32 v48, v236
	v_mov_b32_e32 v49, v237
	v_lshlrev_b32_e32 v58, 16, v42
	v_and_b32_e32 v42, 0xffff0000, v42
	v_lshlrev_b32_e32 v62, 16, v46
	v_and_b32_e32 v46, 0xffff0000, v46
	v_fmac_f32_e32 v42, v55, v46
	v_mul_f32_e32 v46, 0x3d372713, v42
	v_mul_f32_e32 v46, v42, v46
	v_fma_f32 v46, v42, v46, v42
	v_mul_f32_e32 v46, 0x3f4c422a, v46
	v_add_f32_e32 v46, v46, v46
	v_mul_f32_e32 v46, 0xbfb8aa3b, v46
	v_exp_f32_e32 v46, v46
	v_lshlrev_b32_e32 v59, 16, v43
	v_and_b32_e32 v43, 0xffff0000, v43
	v_lshlrev_b32_e32 v63, 16, v47
	v_add_f32_e32 v46, 1.0, v46
	v_rcp_f32_e32 v46, v46
	v_and_b32_e32 v47, 0xffff0000, v47
	v_fmac_f32_e32 v59, v56, v63
	v_fmac_f32_e32 v43, v57, v47
	v_fmac_f32_e32 v58, v54, v62
	v_mul_f32_e32 v42, v42, v46
	v_mul_f32_e32 v46, 0x3d372713, v59
	v_mul_f32_e32 v47, 0x3d372713, v43
	v_mul_f32_e32 v54, 0x3d372713, v58
	v_mul_f32_e32 v46, v59, v46
	v_mul_f32_e32 v47, v43, v47
	v_mul_f32_e32 v54, v58, v54
	v_fma_f32 v46, v59, v46, v59
	v_fma_f32 v47, v43, v47, v43
	v_fma_f32 v54, v58, v54, v58
	v_mul_f32_e32 v46, 0x3f4c422a, v46
	v_mul_f32_e32 v47, 0x3f4c422a, v47
	v_mul_f32_e32 v54, 0x3f4c422a, v54
	v_add_f32_e32 v46, v46, v46
	v_add_f32_e32 v47, v47, v47
	v_add_f32_e32 v54, v54, v54
	v_mul_f32_e32 v46, 0xbfb8aa3b, v46
	v_mul_f32_e32 v47, 0xbfb8aa3b, v47
	v_mul_f32_e32 v54, 0xbfb8aa3b, v54
	v_exp_f32_e32 v46, v46
	v_exp_f32_e32 v47, v47
	v_exp_f32_e32 v54, v54
	v_lshlrev_b32_e32 v60, 16, v44
	v_add_f32_e32 v46, 1.0, v46
	v_add_f32_e32 v47, 1.0, v47
	v_add_f32_e32 v54, 1.0, v54
	v_rcp_f32_e32 v46, v46
	v_rcp_f32_e32 v47, v47
	v_rcp_f32_e32 v54, v54
	v_and_b32_e32 v44, 0xffff0000, v44
	v_lshlrev_b32_e32 v64, 16, v48
	v_and_b32_e32 v48, 0xffff0000, v48
	v_mul_f32_e32 v46, v59, v46
	v_mul_f32_e32 v43, v43, v47
	v_fmac_f32_e32 v60, v50, v64
	v_fmac_f32_e32 v44, v51, v48
	v_mul_f32_e32 v54, v58, v54
	v_cvt_pk_bf16_f32 v42, v54, v42
	v_cvt_pk_bf16_f32 v43, v46, v43
	v_mul_f32_e32 v46, 0x3d372713, v60
	v_mul_f32_e32 v47, 0x3d372713, v44
	v_mul_f32_e32 v46, v60, v46
	v_mul_f32_e32 v47, v44, v47
	v_fma_f32 v46, v60, v46, v60
	v_fma_f32 v47, v44, v47, v44
	v_mul_f32_e32 v46, 0x3f4c422a, v46
	v_mul_f32_e32 v47, 0x3f4c422a, v47
	v_add_f32_e32 v46, v46, v46
	v_add_f32_e32 v47, v47, v47
	v_mul_f32_e32 v46, 0xbfb8aa3b, v46
	v_mul_f32_e32 v47, 0xbfb8aa3b, v47
	v_exp_f32_e32 v46, v46
	v_exp_f32_e32 v47, v47
	v_lshlrev_b32_e32 v61, 16, v45
	v_and_b32_e32 v45, 0xffff0000, v45
	v_add_f32_e32 v46, 1.0, v46
	v_add_f32_e32 v47, 1.0, v47
	v_rcp_f32_e32 v46, v46
	v_rcp_f32_e32 v47, v47
	v_lshlrev_b32_e32 v65, 16, v49
	v_and_b32_e32 v49, 0xffff0000, v49
	v_mul_f32_e32 v46, v60, v46
	v_mul_f32_e32 v44, v44, v47
	v_fmac_f32_e32 v61, v52, v65
	v_fmac_f32_e32 v45, v53, v49
	v_cvt_pk_bf16_f32 v44, v46, v44
	v_mul_f32_e32 v46, 0x3d372713, v61
	v_mul_f32_e32 v47, 0x3d372713, v45
	v_mul_f32_e32 v46, v61, v46
	v_mul_f32_e32 v47, v45, v47
	v_fma_f32 v46, v61, v46, v61
	v_fma_f32 v47, v45, v47, v45
	v_mul_f32_e32 v46, 0x3f4c422a, v46
	v_mul_f32_e32 v47, 0x3f4c422a, v47
	v_add_f32_e32 v46, v46, v46
	v_add_f32_e32 v47, v47, v47
	v_mul_f32_e32 v46, 0xbfb8aa3b, v46
	v_mul_f32_e32 v47, 0xbfb8aa3b, v47
	v_exp_f32_e32 v46, v46
	v_exp_f32_e32 v47, v47
	v_add_f32_e32 v46, 1.0, v46
	v_add_f32_e32 v47, 1.0, v47
	v_rcp_f32_e32 v46, v46
	v_rcp_f32_e32 v47, v47
	v_mul_f32_e32 v46, v61, v46
	v_mul_f32_e32 v45, v45, v47
	v_cvt_pk_bf16_f32 v45, v46, v45
	ds_read_b128 v[54:57], v246 offset:272
	ds_read_b128 v[58:61], v246 offset:256
	s_waitcnt vmcnt(10) lgkmcnt(0)
; __device__ __forceinline__ unsigned cvt_pk_bf16(float lo, float hi) { unsigned r; asm volatile("v_cvt_pk_bf16_f32 %0, %1, %2" : "=v"(r) : "v"(lo), "v"(hi)); return r; }
; __device__ __forceinline__ float gelu_tanh(float x) { const float u = 0.7978845608028654f * (x + 0.044715f * x * x * x); return x * sigm(2.f * u); }
; #define UNPK8(VV_, XX_) float XX_[8] = {bflo((VV_).x), bfhi((VV_).x), bflo((VV_).y), bfhi((VV_).y), bflo((VV_).z), bfhi((VV_).z), bflo((VV_).w), bfhi((VV_).w)}
; __device__ __forceinline__ void glu_task(int t, int l, const float* s5d, const bf16_t* P, const bf16_t* YB, const bf16_t* WGLU, bf16_t* Z1, int fr, int fq) {
;     ...
;     for (int tb = 0; tb < 2; ++tb) { const size_t row = row0 + tb * 16;
; #pragma unroll
;         for (int ks = 0; ks < 8; ++ks) { const int k0 = ks * 32 + fq * 8; const u32x4 yw = ld8(YB + row * 256 + k0), uw = ld8(P + row * INP + OFF_S5 + k0);
;             const f32x4 d0 = *(const f32x4*)(s5d + l * 256 + k0), d1 = *(const f32x4*)(s5d + l * 256 + k0 + 4); UNPK8(yw, y); UNPK8(uw, u); u32x4 o;
;             o.x = cvt_pk_bf16(gelu_tanh(y[0] + d0[0] * u[0]), gelu_tanh(y[1] + d0[1] * u[1])); o.y = cvt_pk_bf16(gelu_tanh(y[2] + d0[2] * u[2]), gelu_tanh(y[3] + d0[3] * u[3]));
;             o.z = cvt_pk_bf16(gelu_tanh(y[4] + d1[0] * u[4]), gelu_tanh(y[5] + d1[1] * u[5])); o.w = cvt_pk_bf16(gelu_tanh(y[6] + d1[2] * u[6]), gelu_tanh(y[7] + d1[3] * u[7]));
;             bfr[tb][ks] = asfrag(o); } }
	v_mov_b32_e32 v46, v238
	v_mov_b32_e32 v47, v239
	v_mov_b32_e32 v48, v240
	v_mov_b32_e32 v49, v241
	v_mov_b32_e32 v50, v242
	v_mov_b32_e32 v51, v243
	v_mov_b32_e32 v52, v244
	v_mov_b32_e32 v53, v245
	v_lshlrev_b32_e32 v62, 16, v46
	v_and_b32_e32 v46, 0xffff0000, v46
	v_lshlrev_b32_e32 v78, 16, v50
	v_and_b32_e32 v50, 0xffff0000, v50
	v_fmac_f32_e32 v46, v59, v50
	v_mul_f32_e32 v50, 0x3d372713, v46
	v_mul_f32_e32 v50, v46, v50
	v_fma_f32 v50, v46, v50, v46
	v_mul_f32_e32 v50, 0x3f4c422a, v50
	v_add_f32_e32 v50, v50, v50
	v_mul_f32_e32 v50, 0xbfb8aa3b, v50
	v_exp_f32_e32 v50, v50
	v_lshlrev_b32_e32 v63, 16, v47
	v_and_b32_e32 v47, 0xffff0000, v47
	v_lshlrev_b32_e32 v79, 16, v51
	v_add_f32_e32 v50, 1.0, v50
	v_rcp_f32_e32 v50, v50
	v_and_b32_e32 v51, 0xffff0000, v51
	v_fmac_f32_e32 v63, v60, v79
	v_fmac_f32_e32 v47, v61, v51
	v_fmac_f32_e32 v62, v58, v78
	v_mul_f32_e32 v46, v46, v50
	v_mul_f32_e32 v50, 0x3d372713, v63
	v_mul_f32_e32 v51, 0x3d372713, v47
	v_mul_f32_e32 v58, 0x3d372713, v62
	v_mul_f32_e32 v50, v63, v50
	v_mul_f32_e32 v51, v47, v51
	v_mul_f32_e32 v58, v62, v58
	v_fma_f32 v50, v63, v50, v63
	v_fma_f32 v51, v47, v51, v47
	v_fma_f32 v58, v62, v58, v62
	v_mul_f32_e32 v50, 0x3f4c422a, v50
	v_mul_f32_e32 v51, 0x3f4c422a, v51
	v_mul_f32_e32 v58, 0x3f4c422a, v58
	v_add_f32_e32 v50, v50, v50
	v_add_f32_e32 v51, v51, v51
	v_add_f32_e32 v58, v58, v58
	v_mul_f32_e32 v50, 0xbfb8aa3b, v50
	v_mul_f32_e32 v51, 0xbfb8aa3b, v51
	v_mul_f32_e32 v58, 0xbfb8aa3b, v58
	v_exp_f32_e32 v50, v50
	v_exp_f32_e32 v51, v51
	v_exp_f32_e32 v58, v58
	v_lshlrev_b32_e32 v64, 16, v48
	v_add_f32_e32 v50, 1.0, v50
	v_add_f32_e32 v51, 1.0, v51
	v_add_f32_e32 v58, 1.0, v58
	v_rcp_f32_e32 v50, v50
	v_rcp_f32_e32 v51, v51
	v_rcp_f32_e32 v58, v58
	v_and_b32_e32 v48, 0xffff0000, v48
	v_lshlrev_b32_e32 v80, 16, v52
	v_and_b32_e32 v52, 0xffff0000, v52
	v_mul_f32_e32 v50, v63, v50
	v_mul_f32_e32 v47, v47, v51
	v_fmac_f32_e32 v64, v54, v80
	v_fmac_f32_e32 v48, v55, v52
	v_mul_f32_e32 v58, v62, v58
	v_cvt_pk_bf16_f32 v46, v58, v46
	v_cvt_pk_bf16_f32 v47, v50, v47
	v_mul_f32_e32 v50, 0x3d372713, v64
	v_mul_f32_e32 v51, 0x3d372713, v48
	v_mul_f32_e32 v50, v64, v50
	v_mul_f32_e32 v51, v48, v51
	v_fma_f32 v50, v64, v50, v64
	v_fma_f32 v51, v48, v51, v48
	v_mul_f32_e32 v50, 0x3f4c422a, v50
	v_mul_f32_e32 v51, 0x3f4c422a, v51
	v_add_f32_e32 v50, v50, v50
	v_add_f32_e32 v51, v51, v51
	v_mul_f32_e32 v50, 0xbfb8aa3b, v50
	v_mul_f32_e32 v51, 0xbfb8aa3b, v51
	v_exp_f32_e32 v50, v50
	v_exp_f32_e32 v51, v51
	v_lshlrev_b32_e32 v65, 16, v49
	v_and_b32_e32 v49, 0xffff0000, v49
	v_add_f32_e32 v50, 1.0, v50
	v_add_f32_e32 v51, 1.0, v51
	v_rcp_f32_e32 v50, v50
	v_rcp_f32_e32 v51, v51
	v_lshlrev_b32_e32 v81, 16, v53
	v_and_b32_e32 v53, 0xffff0000, v53
	v_mul_f32_e32 v50, v64, v50
	v_mul_f32_e32 v48, v48, v51
	v_fmac_f32_e32 v65, v56, v81
	v_fmac_f32_e32 v49, v57, v53
	v_cvt_pk_bf16_f32 v48, v50, v48
	v_mul_f32_e32 v50, 0x3d372713, v65
	v_mul_f32_e32 v51, 0x3d372713, v49
	v_mul_f32_e32 v50, v65, v50
	v_mul_f32_e32 v51, v49, v51
	v_fma_f32 v50, v65, v50, v65
	v_fma_f32 v51, v49, v51, v49
	v_mul_f32_e32 v50, 0x3f4c422a, v50
	v_mul_f32_e32 v51, 0x3f4c422a, v51
	v_add_f32_e32 v50, v50, v50
	v_add_f32_e32 v51, v51, v51
	v_mul_f32_e32 v50, 0xbfb8aa3b, v50
	v_mul_f32_e32 v51, 0xbfb8aa3b, v51
	v_exp_f32_e32 v50, v50
	v_exp_f32_e32 v51, v51
	v_add_f32_e32 v50, 1.0, v50
	v_add_f32_e32 v51, 1.0, v51
	v_rcp_f32_e32 v50, v50
	v_rcp_f32_e32 v51, v51
	v_mul_f32_e32 v50, v65, v50
	v_mul_f32_e32 v49, v49, v51
	v_cvt_pk_bf16_f32 v49, v50, v49
	ds_read_b128 v[58:61], v246 offset:400
	ds_read_b128 v[62:65], v246 offset:384
	s_waitcnt vmcnt(8) lgkmcnt(0)
	v_mov_b32_e32 v50, v168
	v_mov_b32_e32 v51, v169
	v_mov_b32_e32 v52, v170
	v_mov_b32_e32 v53, v171
	v_mov_b32_e32 v54, v188
	v_mov_b32_e32 v55, v189
	v_mov_b32_e32 v56, v190
	v_mov_b32_e32 v57, v191
	v_lshlrev_b32_e32 v78, 16, v50
	v_and_b32_e32 v50, 0xffff0000, v50
	v_lshlrev_b32_e32 v82, 16, v54
	v_and_b32_e32 v54, 0xffff0000, v54
	v_fmac_f32_e32 v50, v63, v54
	v_mul_f32_e32 v54, 0x3d372713, v50
	v_mul_f32_e32 v54, v50, v54
	v_fma_f32 v54, v50, v54, v50
	v_mul_f32_e32 v54, 0x3f4c422a, v54
	v_add_f32_e32 v54, v54, v54
	v_mul_f32_e32 v54, 0xbfb8aa3b, v54
	v_exp_f32_e32 v54, v54
	v_lshlrev_b32_e32 v79, 16, v51
	v_and_b32_e32 v51, 0xffff0000, v51
	v_lshlrev_b32_e32 v83, 16, v55
	v_add_f32_e32 v54, 1.0, v54
	v_rcp_f32_e32 v54, v54
	v_and_b32_e32 v55, 0xffff0000, v55
	v_fmac_f32_e32 v79, v64, v83
	v_fmac_f32_e32 v51, v65, v55
	v_fmac_f32_e32 v78, v62, v82
	v_mul_f32_e32 v50, v50, v54
	v_mul_f32_e32 v54, 0x3d372713, v79
	v_mul_f32_e32 v55, 0x3d372713, v51
	v_mul_f32_e32 v62, 0x3d372713, v78
	v_mul_f32_e32 v54, v79, v54
	v_mul_f32_e32 v55, v51, v55
	v_mul_f32_e32 v62, v78, v62
	v_fma_f32 v54, v79, v54, v79
	v_fma_f32 v55, v51, v55, v51
	v_fma_f32 v62, v78, v62, v78
	v_mul_f32_e32 v54, 0x3f4c422a, v54
	v_mul_f32_e32 v55, 0x3f4c422a, v55
	v_mul_f32_e32 v62, 0x3f4c422a, v62
	v_add_f32_e32 v54, v54, v54
	v_add_f32_e32 v55, v55, v55
	v_add_f32_e32 v62, v62, v62
	v_mul_f32_e32 v54, 0xbfb8aa3b, v54
	v_mul_f32_e32 v55, 0xbfb8aa3b, v55
	v_mul_f32_e32 v62, 0xbfb8aa3b, v62
	v_exp_f32_e32 v54, v54
	v_exp_f32_e32 v55, v55
	v_exp_f32_e32 v62, v62
	v_lshlrev_b32_e32 v80, 16, v52
	v_add_f32_e32 v54, 1.0, v54
	v_add_f32_e32 v55, 1.0, v55
	v_add_f32_e32 v62, 1.0, v62
	v_rcp_f32_e32 v54, v54
	v_rcp_f32_e32 v55, v55
	v_rcp_f32_e32 v62, v62
	v_and_b32_e32 v52, 0xffff0000, v52
	v_lshlrev_b32_e32 v84, 16, v56
	v_and_b32_e32 v56, 0xffff0000, v56
	v_mul_f32_e32 v54, v79, v54
	v_mul_f32_e32 v51, v51, v55
	v_fmac_f32_e32 v80, v58, v84
	v_fmac_f32_e32 v52, v59, v56
	v_mul_f32_e32 v62, v78, v62
; __device__ __forceinline__ unsigned cvt_pk_bf16(float lo, float hi) { unsigned r; asm volatile("v_cvt_pk_bf16_f32 %0, %1, %2" : "=v"(r) : "v"(lo), "v"(hi)); return r; }
; __device__ __forceinline__ float gelu_tanh(float x) { const float u = 0.7978845608028654f * (x + 0.044715f * x * x * x); return x * sigm(2.f * u); }
; #define UNPK8(VV_, XX_) float XX_[8] = {bflo((VV_).x), bfhi((VV_).x), bflo((VV_).y), bfhi((VV_).y), bflo((VV_).z), bfhi((VV_).z), bflo((VV_).w), bfhi((VV_).w)}
; __device__ __forceinline__ void glu_task(int t, int l, const float* s5d, const bf16_t* P, const bf16_t* YB, const bf16_t* WGLU, bf16_t* Z1, int fr, int fq) {
;     ...
;     for (int tb = 0; tb < 2; ++tb) { const size_t row = row0 + tb * 16;
; #pragma unroll
;         for (int ks = 0; ks < 8; ++ks) { const int k0 = ks * 32 + fq * 8; const u32x4 yw = ld8(YB + row * 256 + k0), uw = ld8(P + row * INP + OFF_S5 + k0);
;             const f32x4 d0 = *(const f32x4*)(s5d + l * 256 + k0), d1 = *(const f32x4*)(s5d + l * 256 + k0 + 4); UNPK8(yw, y); UNPK8(uw, u); u32x4 o;
;             o.x = cvt_pk_bf16(gelu_tanh(y[0] + d0[0] * u[0]), gelu_tanh(y[1] + d0[1] * u[1])); o.y = cvt_pk_bf16(gelu_tanh(y[2] + d0[2] * u[2]), gelu_tanh(y[3] + d0[3] * u[3]));
;             o.z = cvt_pk_bf16(gelu_tanh(y[4] + d1[0] * u[4]), gelu_tanh(y[5] + d1[1] * u[5])); o.w = cvt_pk_bf16(gelu_tanh(y[6] + d1[2] * u[6]), gelu_tanh(y[7] + d1[3] * u[7]));
;             bfr[tb][ks] = asfrag(o); } }
	v_cvt_pk_bf16_f32 v50, v62, v50
	v_cvt_pk_bf16_f32 v51, v54, v51
	v_mul_f32_e32 v54, 0x3d372713, v80
	v_mul_f32_e32 v55, 0x3d372713, v52
	v_mul_f32_e32 v54, v80, v54
	v_mul_f32_e32 v55, v52, v55
	v_fma_f32 v54, v80, v54, v80
	v_fma_f32 v55, v52, v55, v52
	v_mul_f32_e32 v54, 0x3f4c422a, v54
	v_mul_f32_e32 v55, 0x3f4c422a, v55
	v_add_f32_e32 v54, v54, v54
	v_add_f32_e32 v55, v55, v55
	v_mul_f32_e32 v54, 0xbfb8aa3b, v54
	v_mul_f32_e32 v55, 0xbfb8aa3b, v55
	v_exp_f32_e32 v54, v54
	v_exp_f32_e32 v55, v55
	v_lshlrev_b32_e32 v81, 16, v53
	v_and_b32_e32 v53, 0xffff0000, v53
	v_add_f32_e32 v54, 1.0, v54
	v_add_f32_e32 v55, 1.0, v55
	v_rcp_f32_e32 v54, v54
	v_rcp_f32_e32 v55, v55
	v_lshlrev_b32_e32 v85, 16, v57
	v_and_b32_e32 v57, 0xffff0000, v57
	v_mul_f32_e32 v54, v80, v54
	v_mul_f32_e32 v52, v52, v55
	v_fmac_f32_e32 v81, v60, v85
	v_fmac_f32_e32 v53, v61, v57
	v_cvt_pk_bf16_f32 v52, v54, v52
	v_mul_f32_e32 v54, 0x3d372713, v81
	v_mul_f32_e32 v55, 0x3d372713, v53
	v_mul_f32_e32 v54, v81, v54
	v_mul_f32_e32 v55, v53, v55
	v_fma_f32 v54, v81, v54, v81
	v_fma_f32 v55, v53, v55, v53
	v_mul_f32_e32 v54, 0x3f4c422a, v54
	v_mul_f32_e32 v55, 0x3f4c422a, v55
	v_add_f32_e32 v54, v54, v54
	v_add_f32_e32 v55, v55, v55
	v_mul_f32_e32 v54, 0xbfb8aa3b, v54
	v_mul_f32_e32 v55, 0xbfb8aa3b, v55
	v_exp_f32_e32 v54, v54
	v_exp_f32_e32 v55, v55
	v_add_f32_e32 v54, 1.0, v54
	v_add_f32_e32 v55, 1.0, v55
	v_rcp_f32_e32 v54, v54
	v_rcp_f32_e32 v55, v55
	v_mul_f32_e32 v54, v81, v54
	v_mul_f32_e32 v53, v53, v55
	v_cvt_pk_bf16_f32 v53, v54, v53
	ds_read_b128 v[62:65], v246 offset:528
	ds_read_b128 v[78:81], v246 offset:512
	s_waitcnt vmcnt(6) lgkmcnt(0)
	v_mov_b32_e32 v54, v98
	v_mov_b32_e32 v55, v99
	v_mov_b32_e32 v56, v100
	v_mov_b32_e32 v57, v101
	v_mov_b32_e32 v58, v102
	v_mov_b32_e32 v59, v103
	v_mov_b32_e32 v60, v104
	v_mov_b32_e32 v61, v105
	v_lshlrev_b32_e32 v82, 16, v54
	v_and_b32_e32 v54, 0xffff0000, v54
	v_lshlrev_b32_e32 v86, 16, v58
	v_and_b32_e32 v58, 0xffff0000, v58
	v_fmac_f32_e32 v54, v79, v58
	v_mul_f32_e32 v58, 0x3d372713, v54
	v_mul_f32_e32 v58, v54, v58
	v_fma_f32 v58, v54, v58, v54
	v_mul_f32_e32 v58, 0x3f4c422a, v58
	v_add_f32_e32 v58, v58, v58
	v_mul_f32_e32 v58, 0xbfb8aa3b, v58
	v_exp_f32_e32 v58, v58
	v_lshlrev_b32_e32 v83, 16, v55
	v_and_b32_e32 v55, 0xffff0000, v55
	v_lshlrev_b32_e32 v87, 16, v59
	v_add_f32_e32 v58, 1.0, v58
	v_rcp_f32_e32 v58, v58
	v_and_b32_e32 v59, 0xffff0000, v59
	v_fmac_f32_e32 v83, v80, v87
	v_fmac_f32_e32 v55, v81, v59
	v_fmac_f32_e32 v82, v78, v86
	v_mul_f32_e32 v54, v54, v58
	v_mul_f32_e32 v58, 0x3d372713, v83
	v_mul_f32_e32 v59, 0x3d372713, v55
	v_mul_f32_e32 v78, 0x3d372713, v82
	v_mul_f32_e32 v58, v83, v58
	v_mul_f32_e32 v59, v55, v59
	v_mul_f32_e32 v78, v82, v78
	v_fma_f32 v58, v83, v58, v83
	v_fma_f32 v59, v55, v59, v55
	v_fma_f32 v78, v82, v78, v82
	v_mul_f32_e32 v58, 0x3f4c422a, v58
	v_mul_f32_e32 v59, 0x3f4c422a, v59
	v_mul_f32_e32 v78, 0x3f4c422a, v78
	v_add_f32_e32 v58, v58, v58
	v_add_f32_e32 v59, v59, v59
	v_add_f32_e32 v78, v78, v78
	v_mul_f32_e32 v58, 0xbfb8aa3b, v58
	v_mul_f32_e32 v59, 0xbfb8aa3b, v59
	v_mul_f32_e32 v78, 0xbfb8aa3b, v78
	v_exp_f32_e32 v58, v58
	v_exp_f32_e32 v59, v59
	v_exp_f32_e32 v78, v78
	v_lshlrev_b32_e32 v84, 16, v56
	v_add_f32_e32 v58, 1.0, v58
	v_add_f32_e32 v59, 1.0, v59
	v_add_f32_e32 v78, 1.0, v78
	v_rcp_f32_e32 v58, v58
	v_rcp_f32_e32 v59, v59
	v_rcp_f32_e32 v78, v78
	v_and_b32_e32 v56, 0xffff0000, v56
	v_lshlrev_b32_e32 v88, 16, v60
	v_and_b32_e32 v60, 0xffff0000, v60
	v_mul_f32_e32 v58, v83, v58
	v_mul_f32_e32 v55, v55, v59
	v_fmac_f32_e32 v84, v62, v88
	v_fmac_f32_e32 v56, v63, v60
	v_mul_f32_e32 v78, v82, v78
	v_cvt_pk_bf16_f32 v54, v78, v54
	v_cvt_pk_bf16_f32 v55, v58, v55
	v_mul_f32_e32 v58, 0x3d372713, v84
	v_mul_f32_e32 v59, 0x3d372713, v56
	v_mul_f32_e32 v58, v84, v58
	v_mul_f32_e32 v59, v56, v59
	v_fma_f32 v58, v84, v58, v84
	v_fma_f32 v59, v56, v59, v56
	v_mul_f32_e32 v58, 0x3f4c422a, v58
	v_mul_f32_e32 v59, 0x3f4c422a, v59
	v_add_f32_e32 v58, v58, v58
	v_add_f32_e32 v59, v59, v59
	v_mul_f32_e32 v58, 0xbfb8aa3b, v58
	v_mul_f32_e32 v59, 0xbfb8aa3b, v59
	v_exp_f32_e32 v58, v58
	v_exp_f32_e32 v59, v59
	v_lshlrev_b32_e32 v85, 16, v57
	v_and_b32_e32 v57, 0xffff0000, v57
	v_add_f32_e32 v58, 1.0, v58
	v_add_f32_e32 v59, 1.0, v59
	v_rcp_f32_e32 v58, v58
	v_rcp_f32_e32 v59, v59
	v_lshlrev_b32_e32 v89, 16, v61
	v_and_b32_e32 v61, 0xffff0000, v61
	v_mul_f32_e32 v58, v84, v58
	v_mul_f32_e32 v56, v56, v59
	v_fmac_f32_e32 v85, v64, v89
	v_fmac_f32_e32 v57, v65, v61
	v_cvt_pk_bf16_f32 v56, v58, v56
	v_mul_f32_e32 v58, 0x3d372713, v85
	v_mul_f32_e32 v59, 0x3d372713, v57
	v_mul_f32_e32 v58, v85, v58
	v_mul_f32_e32 v59, v57, v59
	v_fma_f32 v58, v85, v58, v85
	v_fma_f32 v59, v57, v59, v57
	v_mul_f32_e32 v58, 0x3f4c422a, v58
	v_mul_f32_e32 v59, 0x3f4c422a, v59
	v_add_f32_e32 v58, v58, v58
	v_add_f32_e32 v59, v59, v59
	v_mul_f32_e32 v58, 0xbfb8aa3b, v58
	v_mul_f32_e32 v59, 0xbfb8aa3b, v59
	v_exp_f32_e32 v58, v58
	v_exp_f32_e32 v59, v59
	v_add_f32_e32 v58, 1.0, v58
	v_add_f32_e32 v59, 1.0, v59
	v_rcp_f32_e32 v58, v58
	v_rcp_f32_e32 v59, v59
	v_mul_f32_e32 v58, v85, v58
	v_mul_f32_e32 v57, v57, v59
	v_cvt_pk_bf16_f32 v57, v58, v57
	ds_read_b128 v[78:81], v246 offset:656
	ds_read_b128 v[82:85], v246 offset:640
	s_waitcnt vmcnt(4) lgkmcnt(0)
; __device__ __forceinline__ unsigned cvt_pk_bf16(float lo, float hi) { unsigned r; asm volatile("v_cvt_pk_bf16_f32 %0, %1, %2" : "=v"(r) : "v"(lo), "v"(hi)); return r; }
; __device__ __forceinline__ float gelu_tanh(float x) { const float u = 0.7978845608028654f * (x + 0.044715f * x * x * x); return x * sigm(2.f * u); }
; #define UNPK8(VV_, XX_) float XX_[8] = {bflo((VV_).x), bfhi((VV_).x), bflo((VV_).y), bfhi((VV_).y), bflo((VV_).z), bfhi((VV_).z), bflo((VV_).w), bfhi((VV_).w)}
; __device__ __forceinline__ void glu_task(int t, int l, const float* s5d, const bf16_t* P, const bf16_t* YB, const bf16_t* WGLU, bf16_t* Z1, int fr, int fq) {
;     ...
;     for (int tb = 0; tb < 2; ++tb) { const size_t row = row0 + tb * 16;
; #pragma unroll
;         for (int ks = 0; ks < 8; ++ks) { const int k0 = ks * 32 + fq * 8; const u32x4 yw = ld8(YB + row * 256 + k0), uw = ld8(P + row * INP + OFF_S5 + k0);
;             const f32x4 d0 = *(const f32x4*)(s5d + l * 256 + k0), d1 = *(const f32x4*)(s5d + l * 256 + k0 + 4); UNPK8(yw, y); UNPK8(uw, u); u32x4 o;
;             o.x = cvt_pk_bf16(gelu_tanh(y[0] + d0[0] * u[0]), gelu_tanh(y[1] + d0[1] * u[1])); o.y = cvt_pk_bf16(gelu_tanh(y[2] + d0[2] * u[2]), gelu_tanh(y[3] + d0[3] * u[3]));
;             o.z = cvt_pk_bf16(gelu_tanh(y[4] + d1[0] * u[4]), gelu_tanh(y[5] + d1[1] * u[5])); o.w = cvt_pk_bf16(gelu_tanh(y[6] + d1[2] * u[6]), gelu_tanh(y[7] + d1[3] * u[7]));
;             bfr[tb][ks] = asfrag(o); } }
	v_mov_b32_e32 v58, v106
	v_mov_b32_e32 v59, v107
	v_mov_b32_e32 v60, v108
	v_mov_b32_e32 v61, v109
	v_mov_b32_e32 v62, v110
	v_mov_b32_e32 v63, v111
	v_mov_b32_e32 v64, v112
	v_mov_b32_e32 v65, v113
	v_lshlrev_b32_e32 v86, 16, v58
	v_and_b32_e32 v58, 0xffff0000, v58
	v_lshlrev_b32_e32 v90, 16, v62
	v_and_b32_e32 v62, 0xffff0000, v62
	v_fmac_f32_e32 v58, v83, v62
	v_mul_f32_e32 v62, 0x3d372713, v58
	v_mul_f32_e32 v62, v58, v62
	v_fma_f32 v62, v58, v62, v58
	v_mul_f32_e32 v62, 0x3f4c422a, v62
	v_add_f32_e32 v62, v62, v62
	v_mul_f32_e32 v62, 0xbfb8aa3b, v62
	v_exp_f32_e32 v62, v62
	v_lshlrev_b32_e32 v87, 16, v59
	v_and_b32_e32 v59, 0xffff0000, v59
	v_lshlrev_b32_e32 v91, 16, v63
	v_add_f32_e32 v62, 1.0, v62
	v_rcp_f32_e32 v62, v62
	v_and_b32_e32 v63, 0xffff0000, v63
	v_fmac_f32_e32 v87, v84, v91
	v_fmac_f32_e32 v59, v85, v63
	v_fmac_f32_e32 v86, v82, v90
	v_mul_f32_e32 v58, v58, v62
	v_mul_f32_e32 v62, 0x3d372713, v87
	v_mul_f32_e32 v63, 0x3d372713, v59
	v_mul_f32_e32 v82, 0x3d372713, v86
	v_mul_f32_e32 v62, v87, v62
	v_mul_f32_e32 v63, v59, v63
	v_mul_f32_e32 v82, v86, v82
	v_fma_f32 v62, v87, v62, v87
	v_fma_f32 v63, v59, v63, v59
	v_fma_f32 v82, v86, v82, v86
	v_mul_f32_e32 v62, 0x3f4c422a, v62
	v_mul_f32_e32 v63, 0x3f4c422a, v63
	v_mul_f32_e32 v82, 0x3f4c422a, v82
	v_add_f32_e32 v62, v62, v62
	v_add_f32_e32 v63, v63, v63
	v_add_f32_e32 v82, v82, v82
	v_mul_f32_e32 v62, 0xbfb8aa3b, v62
	v_mul_f32_e32 v63, 0xbfb8aa3b, v63
	v_mul_f32_e32 v82, 0xbfb8aa3b, v82
	v_exp_f32_e32 v62, v62
	v_exp_f32_e32 v63, v63
	v_exp_f32_e32 v82, v82
	v_lshlrev_b32_e32 v88, 16, v60
	v_add_f32_e32 v62, 1.0, v62
	v_add_f32_e32 v63, 1.0, v63
	v_add_f32_e32 v82, 1.0, v82
	v_rcp_f32_e32 v62, v62
	v_rcp_f32_e32 v63, v63
	v_rcp_f32_e32 v82, v82
	v_and_b32_e32 v60, 0xffff0000, v60
	v_lshlrev_b32_e32 v92, 16, v64
	v_and_b32_e32 v64, 0xffff0000, v64
	v_mul_f32_e32 v62, v87, v62
	v_mul_f32_e32 v59, v59, v63
	v_fmac_f32_e32 v88, v78, v92
	v_fmac_f32_e32 v60, v79, v64
	v_mul_f32_e32 v82, v86, v82
	v_cvt_pk_bf16_f32 v58, v82, v58
	v_cvt_pk_bf16_f32 v59, v62, v59
	v_mul_f32_e32 v62, 0x3d372713, v88
	v_mul_f32_e32 v63, 0x3d372713, v60
	v_mul_f32_e32 v62, v88, v62
	v_mul_f32_e32 v63, v60, v63
	v_fma_f32 v62, v88, v62, v88
	v_fma_f32 v63, v60, v63, v60
	v_mul_f32_e32 v62, 0x3f4c422a, v62
	v_mul_f32_e32 v63, 0x3f4c422a, v63
	v_add_f32_e32 v62, v62, v62
	v_add_f32_e32 v63, v63, v63
	v_mul_f32_e32 v62, 0xbfb8aa3b, v62
	v_mul_f32_e32 v63, 0xbfb8aa3b, v63
	v_exp_f32_e32 v62, v62
	v_exp_f32_e32 v63, v63
	v_lshlrev_b32_e32 v89, 16, v61
	v_and_b32_e32 v61, 0xffff0000, v61
	v_add_f32_e32 v62, 1.0, v62
	v_add_f32_e32 v63, 1.0, v63
	v_rcp_f32_e32 v62, v62
	v_rcp_f32_e32 v63, v63
	v_lshlrev_b32_e32 v93, 16, v65
	v_and_b32_e32 v65, 0xffff0000, v65
	v_mul_f32_e32 v62, v88, v62
	v_mul_f32_e32 v60, v60, v63
	v_fmac_f32_e32 v89, v80, v93
	v_fmac_f32_e32 v61, v81, v65
	v_cvt_pk_bf16_f32 v60, v62, v60
	v_mul_f32_e32 v62, 0x3d372713, v89
	v_mul_f32_e32 v63, 0x3d372713, v61
	v_mul_f32_e32 v62, v89, v62
	v_mul_f32_e32 v63, v61, v63
	v_fma_f32 v62, v89, v62, v89
	v_fma_f32 v63, v61, v63, v61
	v_mul_f32_e32 v62, 0x3f4c422a, v62
	v_mul_f32_e32 v63, 0x3f4c422a, v63
	v_add_f32_e32 v62, v62, v62
	v_add_f32_e32 v63, v63, v63
	v_mul_f32_e32 v62, 0xbfb8aa3b, v62
	v_mul_f32_e32 v63, 0xbfb8aa3b, v63
	v_exp_f32_e32 v62, v62
	v_exp_f32_e32 v63, v63
	v_add_f32_e32 v62, 1.0, v62
	v_add_f32_e32 v63, 1.0, v63
	v_rcp_f32_e32 v62, v62
	v_rcp_f32_e32 v63, v63
	v_mul_f32_e32 v62, v89, v62
	v_mul_f32_e32 v61, v61, v63
	v_cvt_pk_bf16_f32 v61, v62, v61
	ds_read_b128 v[82:85], v246 offset:784
	ds_read_b128 v[86:89], v246 offset:768
	s_waitcnt vmcnt(2) lgkmcnt(0)
	v_mov_b32_e32 v62, v118
	v_mov_b32_e32 v63, v119
	v_mov_b32_e32 v64, v120
	v_mov_b32_e32 v65, v121
	v_mov_b32_e32 v78, v122
	v_mov_b32_e32 v79, v123
	v_mov_b32_e32 v80, v124
	v_mov_b32_e32 v81, v125
	v_lshlrev_b32_e32 v90, 16, v62
	v_and_b32_e32 v62, 0xffff0000, v62
	v_lshlrev_b32_e32 v94, 16, v78
	v_and_b32_e32 v78, 0xffff0000, v78
	v_fmac_f32_e32 v62, v87, v78
	v_mul_f32_e32 v78, 0x3d372713, v62
	v_mul_f32_e32 v78, v62, v78
	v_fma_f32 v78, v62, v78, v62
	v_mul_f32_e32 v78, 0x3f4c422a, v78
	v_add_f32_e32 v78, v78, v78
	v_mul_f32_e32 v78, 0xbfb8aa3b, v78
	v_exp_f32_e32 v78, v78
	v_lshlrev_b32_e32 v91, 16, v63
	v_and_b32_e32 v63, 0xffff0000, v63
	v_lshlrev_b32_e32 v95, 16, v79
	v_add_f32_e32 v78, 1.0, v78
	v_rcp_f32_e32 v78, v78
	v_and_b32_e32 v79, 0xffff0000, v79
	v_fmac_f32_e32 v91, v88, v95
	v_fmac_f32_e32 v63, v89, v79
	v_fmac_f32_e32 v90, v86, v94
	v_mul_f32_e32 v62, v62, v78
	v_mul_f32_e32 v78, 0x3d372713, v91
	v_mul_f32_e32 v79, 0x3d372713, v63
	v_mul_f32_e32 v86, 0x3d372713, v90
	v_mul_f32_e32 v78, v91, v78
	v_mul_f32_e32 v79, v63, v79
	v_mul_f32_e32 v86, v90, v86
	v_fma_f32 v78, v91, v78, v91
	v_fma_f32 v79, v63, v79, v63
	v_fma_f32 v86, v90, v86, v90
	v_mul_f32_e32 v78, 0x3f4c422a, v78
	v_mul_f32_e32 v79, 0x3f4c422a, v79
	v_mul_f32_e32 v86, 0x3f4c422a, v86
	v_add_f32_e32 v78, v78, v78
	v_add_f32_e32 v79, v79, v79
	v_add_f32_e32 v86, v86, v86
	v_mul_f32_e32 v78, 0xbfb8aa3b, v78
	v_mul_f32_e32 v79, 0xbfb8aa3b, v79
	v_mul_f32_e32 v86, 0xbfb8aa3b, v86
	v_exp_f32_e32 v78, v78
	v_exp_f32_e32 v79, v79
	v_exp_f32_e32 v86, v86
	v_lshlrev_b32_e32 v92, 16, v64
	v_add_f32_e32 v78, 1.0, v78
	v_add_f32_e32 v79, 1.0, v79
	v_add_f32_e32 v86, 1.0, v86
	v_rcp_f32_e32 v78, v78
	v_rcp_f32_e32 v79, v79
	v_rcp_f32_e32 v86, v86
	v_and_b32_e32 v64, 0xffff0000, v64
	v_lshlrev_b32_e32 v96, 16, v80
	v_and_b32_e32 v80, 0xffff0000, v80
	v_mul_f32_e32 v78, v91, v78
	v_mul_f32_e32 v63, v63, v79
	v_fmac_f32_e32 v92, v82, v96
	v_fmac_f32_e32 v64, v83, v80
	v_mul_f32_e32 v86, v90, v86
; __device__ __forceinline__ unsigned cvt_pk_bf16(float lo, float hi) { unsigned r; asm volatile("v_cvt_pk_bf16_f32 %0, %1, %2" : "=v"(r) : "v"(lo), "v"(hi)); return r; }
; __device__ __forceinline__ float gelu_tanh(float x) { const float u = 0.7978845608028654f * (x + 0.044715f * x * x * x); return x * sigm(2.f * u); }
; #define UNPK8(VV_, XX_) float XX_[8] = {bflo((VV_).x), bfhi((VV_).x), bflo((VV_).y), bfhi((VV_).y), bflo((VV_).z), bfhi((VV_).z), bflo((VV_).w), bfhi((VV_).w)}
; __device__ __forceinline__ void glu_task(int t, int l, const float* s5d, const bf16_t* P, const bf16_t* YB, const bf16_t* WGLU, bf16_t* Z1, int fr, int fq) {
;     ...
;     for (int tb = 0; tb < 2; ++tb) { const size_t row = row0 + tb * 16;
; #pragma unroll
;         for (int ks = 0; ks < 8; ++ks) { const int k0 = ks * 32 + fq * 8; const u32x4 yw = ld8(YB + row * 256 + k0), uw = ld8(P + row * INP + OFF_S5 + k0);
;             const f32x4 d0 = *(const f32x4*)(s5d + l * 256 + k0), d1 = *(const f32x4*)(s5d + l * 256 + k0 + 4); UNPK8(yw, y); UNPK8(uw, u); u32x4 o;
;             o.x = cvt_pk_bf16(gelu_tanh(y[0] + d0[0] * u[0]), gelu_tanh(y[1] + d0[1] * u[1])); o.y = cvt_pk_bf16(gelu_tanh(y[2] + d0[2] * u[2]), gelu_tanh(y[3] + d0[3] * u[3]));
;             o.z = cvt_pk_bf16(gelu_tanh(y[4] + d1[0] * u[4]), gelu_tanh(y[5] + d1[1] * u[5])); o.w = cvt_pk_bf16(gelu_tanh(y[6] + d1[2] * u[6]), gelu_tanh(y[7] + d1[3] * u[7]));
;             bfr[tb][ks] = asfrag(o); } }
;     const bf16_t* wg0 = WGLU + ((size_t)l * 256 + cb0 * 16 + fr) * 256 + fq * 8;
;     bf16x8 wf[2][8];
; #pragma unroll
;     for (int ks = 0; ks < 8; ++ks) wf[0][ks] = asfrag(ld8(wg0 + ks * 32));
;     u32x2 eyw[2][4], euw[2][4], egw[2][4];
; #pragma unroll
;     for (int tb = 0; tb < 2; ++tb)
; #pragma unroll
;         for (int c4 = 0; c4 < 4; ++c4) { const size_t row = row0 + tb * 16; const int n4 = (cb0 + c4) * 16 + fq * 4; eyw[tb][c4] = ld4(YB + row * 256 + n4); euw[tb][c4] = ld4(P + row * INP + OFF_S5 + n4); egw[tb][c4] = ld4(P + row * INP + OFF_GATE + 256 + n4); }
	v_cvt_pk_bf16_f32 v62, v86, v62
	v_cvt_pk_bf16_f32 v63, v78, v63
	v_mul_f32_e32 v78, 0x3d372713, v92
	v_mul_f32_e32 v79, 0x3d372713, v64
	v_mul_f32_e32 v78, v92, v78
	v_mul_f32_e32 v79, v64, v79
	v_fma_f32 v78, v92, v78, v92
	v_fma_f32 v79, v64, v79, v64
	v_mul_f32_e32 v78, 0x3f4c422a, v78
	v_mul_f32_e32 v79, 0x3f4c422a, v79
	v_add_f32_e32 v78, v78, v78
	v_add_f32_e32 v79, v79, v79
	v_mul_f32_e32 v78, 0xbfb8aa3b, v78
	v_mul_f32_e32 v79, 0xbfb8aa3b, v79
	v_exp_f32_e32 v78, v78
	v_exp_f32_e32 v79, v79
	v_lshlrev_b32_e32 v93, 16, v65
	v_and_b32_e32 v65, 0xffff0000, v65
	v_add_f32_e32 v78, 1.0, v78
	v_add_f32_e32 v79, 1.0, v79
	v_rcp_f32_e32 v78, v78
	v_rcp_f32_e32 v79, v79
	v_lshlrev_b32_e32 v97, 16, v81
	v_and_b32_e32 v81, 0xffff0000, v81
	v_mul_f32_e32 v78, v92, v78
	v_mul_f32_e32 v64, v64, v79
	v_fmac_f32_e32 v93, v84, v97
	v_fmac_f32_e32 v65, v85, v81
	v_cvt_pk_bf16_f32 v64, v78, v64
	v_mul_f32_e32 v78, 0x3d372713, v93
	v_mul_f32_e32 v79, 0x3d372713, v65
	v_mul_f32_e32 v78, v93, v78
	v_mul_f32_e32 v79, v65, v79
	v_fma_f32 v78, v93, v78, v93
	v_fma_f32 v79, v65, v79, v65
	v_mul_f32_e32 v78, 0x3f4c422a, v78
	v_mul_f32_e32 v79, 0x3f4c422a, v79
	v_add_f32_e32 v78, v78, v78
	v_add_f32_e32 v79, v79, v79
	v_mul_f32_e32 v78, 0xbfb8aa3b, v78
	v_mul_f32_e32 v79, 0xbfb8aa3b, v79
	v_exp_f32_e32 v78, v78
	v_exp_f32_e32 v79, v79
	v_add_f32_e32 v78, 1.0, v78
	v_add_f32_e32 v79, 1.0, v79
	v_rcp_f32_e32 v78, v78
	v_rcp_f32_e32 v79, v79
	v_mul_f32_e32 v78, v93, v78
	v_mul_f32_e32 v65, v65, v79
	v_cvt_pk_bf16_f32 v65, v78, v65
	s_nop 0
	s_nop 0
	ds_read_b128 v[82:85], v246 offset:912
	ds_read_b128 v[86:89], v246 offset:896
	s_waitcnt vmcnt(0) lgkmcnt(0)
	v_mov_b32_e32 v78, v126
	v_mov_b32_e32 v79, v127
	v_mov_b32_e32 v80, v128
	v_mov_b32_e32 v81, v129
	v_mov_b32_e32 v66, v130
	v_mov_b32_e32 v67, v131
	v_mov_b32_e32 v68, v132
	v_mov_b32_e32 v69, v133
	v_lshlrev_b32_e32 v90, 16, v78
	v_and_b32_e32 v78, 0xffff0000, v78
	v_lshlrev_b32_e32 v94, 16, v66
	v_and_b32_e32 v66, 0xffff0000, v66
	v_fmac_f32_e32 v78, v87, v66
	v_mul_f32_e32 v66, 0x3d372713, v78
	v_mul_f32_e32 v66, v78, v66
	v_fma_f32 v66, v78, v66, v78
	v_mul_f32_e32 v66, 0x3f4c422a, v66
	v_add_f32_e32 v66, v66, v66
	v_mul_f32_e32 v66, 0xbfb8aa3b, v66
	v_exp_f32_e32 v66, v66
	v_lshlrev_b32_e32 v91, 16, v79
	v_and_b32_e32 v79, 0xffff0000, v79
	v_lshlrev_b32_e32 v95, 16, v67
	v_add_f32_e32 v66, 1.0, v66
	v_rcp_f32_e32 v66, v66
	v_and_b32_e32 v67, 0xffff0000, v67
	v_fmac_f32_e32 v91, v88, v95
	v_fmac_f32_e32 v79, v89, v67
	v_fmac_f32_e32 v90, v86, v94
	v_mul_f32_e32 v66, v78, v66
	v_mul_f32_e32 v78, 0x3d372713, v91
	v_mul_f32_e32 v67, 0x3d372713, v79
	v_mul_f32_e32 v86, 0x3d372713, v90
	v_mul_f32_e32 v78, v91, v78
	v_mul_f32_e32 v67, v79, v67
	v_mul_f32_e32 v86, v90, v86
	v_fma_f32 v78, v91, v78, v91
	v_fma_f32 v67, v79, v67, v79
	v_fma_f32 v86, v90, v86, v90
	v_mul_f32_e32 v78, 0x3f4c422a, v78
	v_mul_f32_e32 v67, 0x3f4c422a, v67
	v_mul_f32_e32 v86, 0x3f4c422a, v86
	v_add_f32_e32 v78, v78, v78
	v_add_f32_e32 v67, v67, v67
	v_add_f32_e32 v86, v86, v86
	v_mul_f32_e32 v78, 0xbfb8aa3b, v78
	v_mul_f32_e32 v67, 0xbfb8aa3b, v67
	v_mul_f32_e32 v86, 0xbfb8aa3b, v86
	v_exp_f32_e32 v78, v78
	v_exp_f32_e32 v67, v67
	v_exp_f32_e32 v86, v86
	v_lshlrev_b32_e32 v92, 16, v80
	v_add_f32_e32 v78, 1.0, v78
	v_add_f32_e32 v67, 1.0, v67
	v_add_f32_e32 v86, 1.0, v86
	v_rcp_f32_e32 v78, v78
	v_rcp_f32_e32 v67, v67
	v_rcp_f32_e32 v86, v86
	v_and_b32_e32 v80, 0xffff0000, v80
	v_lshlrev_b32_e32 v96, 16, v68
	v_and_b32_e32 v68, 0xffff0000, v68
	v_mul_f32_e32 v78, v91, v78
	v_mul_f32_e32 v67, v79, v67
	v_fmac_f32_e32 v92, v82, v96
	v_fmac_f32_e32 v80, v83, v68
	v_mul_f32_e32 v86, v90, v86
	v_cvt_pk_bf16_f32 v66, v86, v66
	v_cvt_pk_bf16_f32 v67, v78, v67
	v_mul_f32_e32 v78, 0x3d372713, v92
	v_mul_f32_e32 v68, 0x3d372713, v80
	v_mul_f32_e32 v78, v92, v78
	v_mul_f32_e32 v68, v80, v68
	v_fma_f32 v78, v92, v78, v92
	v_fma_f32 v68, v80, v68, v80
	v_mul_f32_e32 v78, 0x3f4c422a, v78
	v_mul_f32_e32 v68, 0x3f4c422a, v68
	v_add_f32_e32 v78, v78, v78
	v_add_f32_e32 v68, v68, v68
	v_mul_f32_e32 v78, 0xbfb8aa3b, v78
	v_mul_f32_e32 v68, 0xbfb8aa3b, v68
	v_exp_f32_e32 v78, v78
	v_exp_f32_e32 v68, v68
	v_lshlrev_b32_e32 v93, 16, v81
	v_and_b32_e32 v81, 0xffff0000, v81
	v_add_f32_e32 v78, 1.0, v78
	v_add_f32_e32 v68, 1.0, v68
	v_rcp_f32_e32 v78, v78
	v_rcp_f32_e32 v68, v68
	v_lshlrev_b32_e32 v97, 16, v69
	v_and_b32_e32 v69, 0xffff0000, v69
	v_mul_f32_e32 v78, v92, v78
	v_mul_f32_e32 v68, v80, v68
	v_fmac_f32_e32 v93, v84, v97
	v_fmac_f32_e32 v81, v85, v69
	v_cvt_pk_bf16_f32 v68, v78, v68
	v_mul_f32_e32 v78, 0x3d372713, v93
	v_mul_f32_e32 v69, 0x3d372713, v81
	v_mul_f32_e32 v78, v93, v78
	v_mul_f32_e32 v69, v81, v69
	v_fma_f32 v78, v93, v78, v93
	v_fma_f32 v69, v81, v69, v81
	v_mul_f32_e32 v78, 0x3f4c422a, v78
	v_mul_f32_e32 v69, 0x3f4c422a, v69
	v_add_f32_e32 v78, v78, v78
	v_add_f32_e32 v69, v69, v69
	v_mul_f32_e32 v78, 0xbfb8aa3b, v78
	v_mul_f32_e32 v69, 0xbfb8aa3b, v69
	v_exp_f32_e32 v78, v78
	v_exp_f32_e32 v69, v69
	v_mov_b32_e32 v79, v1
	v_add_f32_e32 v78, 1.0, v78
	v_add_f32_e32 v69, 1.0, v69
	v_rcp_f32_e32 v78, v78
	v_rcp_f32_e32 v69, v69
	v_mul_f32_e32 v78, v93, v78
	v_mul_f32_e32 v69, v81, v69
	v_cvt_pk_bf16_f32 v69, v78, v69
	v_or_b32_e32 v78, s5, v176
	v_lshlrev_b32_e32 v78, 9, v78
	v_lshl_add_u64 v[116:117], v[136:137], 0, v[78:79]
	global_load_dwordx4 v[78:81], v[116:117], off
	global_load_dwordx4 v[82:85], v[116:117], off offset:64
	global_load_dwordx4 v[86:89], v[116:117], off offset:128
	global_load_dwordx4 v[90:93], v[116:117], off offset:192
	global_load_dwordx4 v[94:97], v[116:117], off offset:256
	global_load_dwordx4 v[98:101], v[116:117], off offset:320
; __device__ __forceinline__ unsigned cvt_pk_bf16(float lo, float hi) { unsigned r; asm volatile("v_cvt_pk_bf16_f32 %0, %1, %2" : "=v"(r) : "v"(lo), "v"(hi)); return r; }
; __device__ __forceinline__ float bflo(unsigned w) { return __uint_as_float(w << 16); }
; __device__ __forceinline__ void glu_task(int t, int l, const float* s5d, const bf16_t* P, const bf16_t* YB, const bf16_t* WGLU, bf16_t* Z1, int fr, int fq) {
;     ...
;     const bf16_t* wg0 = WGLU + ((size_t)l * 256 + cb0 * 16 + fr) * 256 + fq * 8;
;     bf16x8 wf[2][8];
; #pragma unroll
;     for (int ks = 0; ks < 8; ++ks) wf[0][ks] = asfrag(ld8(wg0 + ks * 32));
;     u32x2 eyw[2][4], euw[2][4], egw[2][4];
; #pragma unroll
;     for (int tb = 0; tb < 2; ++tb)
; #pragma unroll
;         for (int c4 = 0; c4 < 4; ++c4) { const size_t row = row0 + tb * 16; const int n4 = (cb0 + c4) * 16 + fq * 4; eyw[tb][c4] = ld4(YB + row * 256 + n4); euw[tb][c4] = ld4(P + row * INP + OFF_S5 + n4); egw[tb][c4] = ld4(P + row * INP + OFF_GATE + 256 + n4); }
; #pragma unroll
;     for (int c4 = 0; c4 < 4; ++c4) { f32x4 acc[2]; acc[0] = (f32x4){0.f, 0.f, 0.f, 0.f}; acc[1] = acc[0];
;         const int nrow = c4 < 3 ? (c4 + 1) * 16 : 0;
; #pragma unroll
;         for (int ks = 0; ks < 8; ++ks) wf[(c4 + 1) & 1][ks] = asfrag(ld8(wg0 + (size_t)nrow * 256 + ks * 32));
; #pragma unroll
;         for (int ks = 0; ks < 8; ++ks) { acc[0] = MFMA16(wf[c4 & 1][ks], bfr[0][ks], acc[0]); acc[1] = MFMA16(wf[c4 & 1][ks], bfr[1][ks], acc[1]); }
;         const int n4 = (cb0 + c4) * 16 + fq * 4;
;         const f32x4 dd = *(const f32x4*)(s5d + l * 256 + n4);
; #pragma unroll
;         for (int tb = 0; tb < 2; ++tb) { const u32x2 yw = eyw[tb][c4], uw = euw[tb][c4], gw = egw[tb][c4];
;             const float y0 = bflo(yw.x), y1 = bfhi(yw.x), y2 = bflo(yw.y), y3 = bfhi(yw.y), u0 = bflo(uw.x), u1 = bfhi(uw.x), u2 = bflo(uw.y), u3 = bfhi(uw.y);
;             const float g0 = gelu_tanh(y0 + dd[0] * u0), g1 = gelu_tanh(y1 + dd[1] * u1), g2 = gelu_tanh(y2 + dd[2] * u2), g3 = gelu_tanh(y3 + dd[3] * u3);
;             u32x2 w; w.x = cvt_pk_bf16(g0 * sigm(acc[tb][0]) * siluf(bflo(gw.x)), g1 * sigm(acc[tb][1]) * siluf(bfhi(gw.x)));
;             w.y = cvt_pk_bf16(g2 * sigm(acc[tb][2]) * siluf(bflo(gw.y)), g3 * sigm(acc[tb][3]) * siluf(bfhi(gw.y)));
;             *(u32x2*)(Z1 + (row0 + tb * 16) * 256 + n4) = w; } }
	global_load_dwordx4 v[102:105], v[116:117], off offset:384
	global_load_dwordx4 v[106:109], v[116:117], off offset:448
	global_load_dwordx2 v[172:173], v[70:71], off
	global_load_dwordx2 v[192:193], v[72:73], off offset:320
	global_load_dwordx2 v[226:227], v[72:73], off offset:2880
	global_load_dwordx2 v[128:129], v[70:71], off offset:32
	global_load_dwordx2 v[126:127], v[72:73], off offset:352
	global_load_dwordx2 v[124:125], v[72:73], off offset:2912
	global_load_dwordx2 v[170:171], v[70:71], off offset:64
	global_load_dwordx2 v[168:169], v[72:73], off offset:384
	global_load_dwordx2 v[166:167], v[72:73], off offset:2944
	global_load_dwordx2 v[156:157], v[70:71], off offset:96
	global_load_dwordx2 v[148:149], v[72:73], off offset:416
	global_load_dwordx2 v[146:147], v[72:73], off offset:2976
	v_lshl_add_u64 v[70:71], v[74:75], 0, v[158:159]
	v_lshl_add_u64 v[72:73], v[76:77], 0, v[158:159]
	global_load_dwordx2 v[228:229], v[70:71], off
	global_load_dwordx2 v[230:231], v[72:73], off offset:320
	global_load_dwordx2 v[232:233], v[72:73], off offset:2880
	global_load_dwordx2 v[122:123], v[70:71], off offset:32
	global_load_dwordx2 v[120:121], v[72:73], off offset:352
	global_load_dwordx2 v[118:119], v[72:73], off offset:2912
	global_load_dwordx2 v[164:165], v[70:71], off offset:64
	global_load_dwordx2 v[162:163], v[72:73], off offset:384
	global_load_dwordx2 v[160:161], v[72:73], off offset:2944
	global_load_dwordx2 v[144:145], v[70:71], off offset:96
	global_load_dwordx2 v[142:143], v[72:73], off offset:416
	global_load_dwordx2 v[140:141], v[72:73], off offset:2976
	v_add_co_u32_e32 v70, vcc, s33, v116
	s_waitcnt vmcnt(0) lgkmcnt(0)
	v_mfma_f32_16x16x32_bf16 v[74:77], v[78:81], v[38:41], 0
	v_addc_co_u32_e32 v71, vcc, 0, v117, vcc
	global_load_dwordx4 v[110:113], v[70:71], off
	global_load_dwordx4 v[130:133], v[70:71], off offset:64
	global_load_dwordx4 v[180:183], v[70:71], off offset:128
	global_load_dwordx4 v[184:187], v[70:71], off offset:192
	global_load_dwordx4 v[188:191], v[70:71], off offset:256
	global_load_dwordx4 v[214:217], v[70:71], off offset:320
	global_load_dwordx4 v[218:221], v[70:71], off offset:384
	global_load_dwordx4 v[222:225], v[70:71], off offset:448
	v_mfma_f32_16x16x32_bf16 v[70:73], v[78:81], v[2:5], 0
	global_load_dwordx4 v[78:81], v178, s[22:23]
	v_and_b32_e32 v179, 0xffff0000, v129
	v_mfma_f32_16x16x32_bf16 v[70:73], v[82:85], v[6:9], v[70:73]
	v_mfma_f32_16x16x32_bf16 v[74:77], v[82:85], v[42:45], v[74:77]
	v_lshlrev_b32_e32 v84, 16, v172
	v_lshlrev_b32_e32 v85, 16, v192
	v_lshl_add_u64 v[82:83], s[40:41], 0, v[158:159]
	v_mfma_f32_16x16x32_bf16 v[70:73], v[86:89], v[14:17], v[70:73]
	v_lshlrev_b32_e32 v159, 16, v128
	v_and_b32_e32 v128, 0xffff0000, v128
	s_waitcnt vmcnt(0)
	v_fmac_f32_e32 v84, v78, v85
	v_mul_f32_e32 v85, 0x3d372713, v84
	v_mul_f32_e32 v85, v84, v85
	v_fma_f32 v85, v84, v85, v84
	v_mul_f32_e32 v85, 0x3f4c422a, v85
	v_add_f32_e32 v85, v85, v85
	v_mul_f32_e32 v85, 0xbfb8aa3b, v85
	v_exp_f32_e32 v85, v85
	v_mfma_f32_16x16x32_bf16 v[74:77], v[86:89], v[46:49], v[74:77]
	v_and_b32_e32 v86, 0xffff0000, v172
	v_and_b32_e32 v87, 0xffff0000, v192
	v_add_f32_e32 v85, 1.0, v85
	v_rcp_f32_e32 v85, v85
	v_fmac_f32_e32 v86, v79, v87
	v_lshlrev_b32_e32 v88, 16, v173
	v_lshlrev_b32_e32 v89, 16, v193
	v_mul_f32_e32 v85, v84, v85
	v_mul_f32_e32 v84, 0x3d372713, v86
	v_mul_f32_e32 v84, v86, v84
	v_fma_f32 v84, v86, v84, v86
	v_mul_f32_e32 v84, 0x3f4c422a, v84
	v_add_f32_e32 v84, v84, v84
	v_mul_f32_e32 v84, 0xbfb8aa3b, v84
	v_exp_f32_e32 v84, v84
	v_fmac_f32_e32 v88, v80, v89
	v_mfma_f32_16x16x32_bf16 v[70:73], v[90:93], v[18:21], v[70:73]
	v_lshlrev_b32_e32 v172, 16, v129
	v_add_f32_e32 v84, 1.0, v84
	v_rcp_f32_e32 v84, v84
	v_mfma_f32_16x16x32_bf16 v[70:73], v[94:97], v[22:25], v[70:73]
	v_lshlrev_b32_e32 v129, 16, v126
	v_and_b32_e32 v126, 0xffff0000, v126
	v_mul_f32_e32 v87, v86, v84
	v_mul_f32_e32 v84, 0x3d372713, v88
	v_mul_f32_e32 v84, v88, v84
	v_fma_f32 v84, v88, v84, v88
	v_mul_f32_e32 v84, 0x3f4c422a, v84
	v_add_f32_e32 v84, v84, v84
	v_mul_f32_e32 v84, 0xbfb8aa3b, v84
	v_exp_f32_e32 v84, v84
	v_mfma_f32_16x16x32_bf16 v[74:77], v[90:93], v[50:53], v[74:77]
	v_and_b32_e32 v90, 0xffff0000, v173
	v_and_b32_e32 v91, 0xffff0000, v193
	v_add_f32_e32 v84, 1.0, v84
	v_rcp_f32_e32 v84, v84
	v_mfma_f32_16x16x32_bf16 v[70:73], v[98:101], v[26:29], v[70:73]
	v_fmac_f32_e32 v90, v81, v91
	v_and_b32_e32 v86, 0xffff0000, v226
	v_mul_f32_e32 v89, v88, v84
	v_mul_f32_e32 v84, 0x3d372713, v90
	v_mul_f32_e32 v84, v90, v84
	v_mfma_f32_16x16x32_bf16 v[70:73], v[102:105], v[30:33], v[70:73]
	v_fma_f32 v84, v90, v84, v90
	v_mul_f32_e32 v84, 0x3f4c422a, v84
	v_add_f32_e32 v84, v84, v84
	v_mul_f32_e32 v84, 0xbfb8aa3b, v84
	v_mfma_f32_16x16x32_bf16 v[70:73], v[106:109], v[34:37], v[70:73]
	v_exp_f32_e32 v84, v84
	v_lshlrev_b32_e32 v88, 16, v227
	v_lshlrev_b32_e32 v173, 16, v127
	v_mfma_f32_16x16x32_bf16 v[74:77], v[94:97], v[54:57], v[74:77]
	v_add_f32_e32 v84, 1.0, v84
	s_nop 2
	v_mul_f32_e32 v70, 0xbfb8aa3b, v70
	v_rcp_f32_e32 v84, v84
	v_exp_f32_e32 v70, v70
	v_mfma_f32_16x16x32_bf16 v[74:77], v[98:101], v[58:61], v[74:77]
	v_mul_f32_e32 v91, v90, v84
	v_add_f32_e32 v70, 1.0, v70
	v_lshlrev_b32_e32 v84, 16, v226
	v_rcp_f32_e32 v93, v70
	v_mul_f32_e32 v70, 0xbfb8aa3b, v84
	v_exp_f32_e32 v70, v70
	v_and_b32_e32 v90, 0xffff0000, v227
	v_mfma_f32_16x16x32_bf16 v[74:77], v[102:105], v[62:65], v[74:77]
	v_add_f32_e32 v70, 1.0, v70
	v_rcp_f32_e32 v92, v70
	v_mul_f32_e32 v70, 0xbfb8aa3b, v71
	v_exp_f32_e32 v70, v70
	v_mfma_f32_16x16x32_bf16 v[74:77], v[106:109], v[66:69], v[74:77]
	v_mul_f32_e64 v84, v92, v84
	v_mul_f32_e64 v85, v93, v85
	v_add_f32_e32 v70, 1.0, v70
	v_rcp_f32_e32 v71, v70
	v_mul_f32_e32 v70, 0xbfb8aa3b, v86
	v_exp_f32_e32 v70, v70
	v_mul_f32_e32 v84, v84, v85
	s_waitcnt lgkmcnt(0)
; __device__ __forceinline__ unsigned cvt_pk_bf16(float lo, float hi) { unsigned r; asm volatile("v_cvt_pk_bf16_f32 %0, %1, %2" : "=v"(r) : "v"(lo), "v"(hi)); return r; }
; __device__ __forceinline__ float bflo(unsigned w) { return __uint_as_float(w << 16); }
; __device__ __forceinline__ float bfhi(unsigned w) { return __uint_as_float(w & 0xffff0000u); }
; __device__ __forceinline__ float sigm(float x) { return __builtin_amdgcn_rcpf(1.f + __expf(-x)); }
; __device__ __forceinline__ float siluf(float x) { return x * __builtin_amdgcn_rcpf(1.f + __expf(-x)); }
; __device__ __forceinline__ float gelu_tanh(float x) { const float u = 0.7978845608028654f * (x + 0.044715f * x * x * x); return x * sigm(2.f * u); }
; #define MFMA16(a, b, c) __builtin_amdgcn_mfma_f32_16x16x32_bf16((a), (b), (c), 0, 0, 0)
; __device__ __forceinline__ void glu_task(int t, int l, const float* s5d, const bf16_t* P, const bf16_t* YB, const bf16_t* WGLU, bf16_t* Z1, int fr, int fq) {
;     ...
;     for (int c4 = 0; c4 < 4; ++c4) { f32x4 acc[2]; acc[0] = (f32x4){0.f, 0.f, 0.f, 0.f}; acc[1] = acc[0];
;         const int nrow = c4 < 3 ? (c4 + 1) * 16 : 0;
; #pragma unroll
;         for (int ks = 0; ks < 8; ++ks) wf[(c4 + 1) & 1][ks] = asfrag(ld8(wg0 + (size_t)nrow * 256 + ks * 32));
; #pragma unroll
;         for (int ks = 0; ks < 8; ++ks) { acc[0] = MFMA16(wf[c4 & 1][ks], bfr[0][ks], acc[0]); acc[1] = MFMA16(wf[c4 & 1][ks], bfr[1][ks], acc[1]); }
;         const int n4 = (cb0 + c4) * 16 + fq * 4;
;         const f32x4 dd = *(const f32x4*)(s5d + l * 256 + n4);
; #pragma unroll
;         for (int tb = 0; tb < 2; ++tb) { const u32x2 yw = eyw[tb][c4], uw = euw[tb][c4], gw = egw[tb][c4];
;             const float y0 = bflo(yw.x), y1 = bfhi(yw.x), y2 = bflo(yw.y), y3 = bfhi(yw.y), u0 = bflo(uw.x), u1 = bfhi(uw.x), u2 = bflo(uw.y), u3 = bfhi(uw.y);
;             const float g0 = gelu_tanh(y0 + dd[0] * u0), g1 = gelu_tanh(y1 + dd[1] * u1), g2 = gelu_tanh(y2 + dd[2] * u2), g3 = gelu_tanh(y3 + dd[3] * u3);
;             u32x2 w; w.x = cvt_pk_bf16(g0 * sigm(acc[tb][0]) * siluf(bflo(gw.x)), g1 * sigm(acc[tb][1]) * siluf(bfhi(gw.x)));
;             w.y = cvt_pk_bf16(g2 * sigm(acc[tb][2]) * siluf(bflo(gw.y)), g3 * sigm(acc[tb][3]) * siluf(bfhi(gw.y)));
;             *(u32x2*)(Z1 + (row0 + tb * 16) * 256 + n4) = w; } }
	v_mfma_f32_16x16x32_bf16 v[102:105], v[110:113], v[2:5], 0
	v_add_f32_e32 v70, 1.0, v70
	v_rcp_f32_e32 v70, v70
	v_mfma_f32_16x16x32_bf16 v[106:109], v[110:113], v[38:41], 0
	v_mul_f32_e64 v70, v70, v86
	v_mul_f32_e64 v71, v71, v87
	v_mul_f32_e32 v70, v70, v71
	v_mul_f32_e32 v71, 0xbfb8aa3b, v72
	v_mul_f32_e32 v72, 0xbfb8aa3b, v73
	v_exp_f32_e32 v71, v71
	v_exp_f32_e32 v72, v72
	v_cvt_pk_bf16_f32 v70, v84, v70
	v_lshlrev_b32_e32 v86, 16, v231
	v_add_f32_e32 v71, 1.0, v71
	v_add_f32_e32 v72, 1.0, v72
	v_rcp_f32_e32 v85, v71
	v_mul_f32_e32 v71, 0xbfb8aa3b, v88
	v_rcp_f32_e32 v73, v72
	v_mul_f32_e32 v72, 0xbfb8aa3b, v90
	v_exp_f32_e32 v71, v71
	v_exp_f32_e32 v72, v72
	v_and_b32_e32 v87, 0xffff0000, v231
	v_mfma_f32_16x16x32_bf16 v[102:105], v[130:133], v[6:9], v[102:105]
	v_add_f32_e32 v71, 1.0, v71
	v_add_f32_e32 v72, 1.0, v72
	v_rcp_f32_e32 v84, v71
	v_rcp_f32_e32 v72, v72
	v_mfma_f32_16x16x32_bf16 v[106:109], v[130:133], v[42:45], v[106:109]
	v_or_b32_e32 v130, 32, v158
	v_pk_mul_f32 v[84:85], v[84:85], v[88:89]
	v_pk_mul_f32 v[72:73], v[72:73], v[90:91]
	v_mul_f32_e32 v71, v84, v85
	v_mul_f32_e32 v72, v72, v73
	v_cvt_pk_bf16_f32 v71, v71, v72
	v_lshl_add_u64 v[72:73], v[82:83], 0, v[114:115]
	global_store_dwordx2 v[72:73], v[70:71], off
	v_lshlrev_b32_e32 v70, 16, v228
	v_lshlrev_b32_e32 v71, 16, v230
	v_fmac_f32_e32 v70, v78, v71
	v_mul_f32_e32 v71, 0x3d372713, v70
	v_mul_f32_e32 v71, v70, v71
	v_fma_f32 v71, v70, v71, v70
	v_mul_f32_e32 v71, 0x3f4c422a, v71
	v_add_f32_e32 v71, v71, v71
	v_mul_f32_e32 v71, 0xbfb8aa3b, v71
	v_exp_f32_e32 v71, v71
	v_and_b32_e32 v72, 0xffff0000, v228
	v_and_b32_e32 v73, 0xffff0000, v230
	v_fmac_f32_e32 v72, v79, v73
	v_add_f32_e32 v71, 1.0, v71
	v_rcp_f32_e32 v71, v71
	v_lshlrev_b32_e32 v84, 16, v229
	v_fmac_f32_e32 v84, v80, v86
	v_and_b32_e32 v85, 0xffff0000, v229
	v_mul_f32_e32 v71, v70, v71
	v_mul_f32_e32 v70, 0x3d372713, v72
	v_mul_f32_e32 v70, v72, v70
	v_fma_f32 v70, v72, v70, v72
	v_mul_f32_e32 v70, 0x3f4c422a, v70
	v_add_f32_e32 v70, v70, v70
	v_mul_f32_e32 v70, 0xbfb8aa3b, v70
	v_exp_f32_e32 v70, v70
	v_fmac_f32_e32 v85, v81, v87
	v_lshlrev_b32_e32 v78, 16, v233
	v_mfma_f32_16x16x32_bf16 v[102:105], v[180:183], v[14:17], v[102:105]
	v_add_f32_e32 v70, 1.0, v70
	v_rcp_f32_e32 v70, v70
	v_and_b32_e32 v80, 0xffff0000, v233
	v_mfma_f32_16x16x32_bf16 v[106:109], v[180:183], v[46:49], v[106:109]
	v_and_b32_e32 v180, 0xffff0000, v127
	v_mul_f32_e32 v73, v72, v70
	v_mul_f32_e32 v70, 0x3d372713, v84
	v_mul_f32_e32 v70, v84, v70
	v_fma_f32 v70, v84, v70, v84
	v_mul_f32_e32 v70, 0x3f4c422a, v70
	v_add_f32_e32 v70, v70, v70
	v_mul_f32_e32 v70, 0xbfb8aa3b, v70
	v_exp_f32_e32 v70, v70
	v_mfma_f32_16x16x32_bf16 v[102:105], v[184:187], v[18:21], v[102:105]
	v_mov_b32_e32 v131, v1
	v_lshl_add_u64 v[132:133], s[40:41], 0, v[130:131]
	v_add_f32_e32 v70, 1.0, v70
	v_rcp_f32_e32 v70, v70
	v_mfma_f32_16x16x32_bf16 v[106:109], v[184:187], v[50:53], v[106:109]
	v_mul_f32_e32 v79, v84, v70
	v_mul_f32_e32 v70, 0x3d372713, v85
	v_mul_f32_e32 v70, v85, v70
	v_fma_f32 v70, v85, v70, v85
	v_mul_f32_e32 v70, 0x3f4c422a, v70
	v_add_f32_e32 v70, v70, v70
	v_mul_f32_e32 v70, 0xbfb8aa3b, v70
	v_exp_f32_e32 v70, v70
	v_mfma_f32_16x16x32_bf16 v[102:105], v[188:191], v[22:25], v[102:105]
	v_add_f32_e32 v70, 1.0, v70
	v_rcp_f32_e32 v70, v70
	v_mfma_f32_16x16x32_bf16 v[106:109], v[188:191], v[54:57], v[106:109]
	v_mul_f32_e32 v81, v85, v70
	v_mul_f32_e32 v70, 0xbfb8aa3b, v74
	v_exp_f32_e32 v70, v70
	v_mfma_f32_16x16x32_bf16 v[102:105], v[214:217], v[26:29], v[102:105]
	v_add_f32_e32 v70, 1.0, v70
	v_rcp_f32_e32 v85, v70
	v_lshlrev_b32_e32 v70, 16, v232
	v_mul_f32_e32 v72, 0xbfb8aa3b, v70
	v_exp_f32_e32 v72, v72
	v_mfma_f32_16x16x32_bf16 v[106:109], v[214:217], v[58:61], v[106:109]
	v_add_f32_e32 v72, 1.0, v72
	v_rcp_f32_e32 v84, v72
	v_and_b32_e32 v72, 0xffff0000, v232
	v_mfma_f32_16x16x32_bf16 v[102:105], v[218:221], v[30:33], v[102:105]
	v_mul_f32_e64 v70, v84, v70
	v_mul_f32_e64 v71, v85, v71
	v_mul_f32_e32 v74, v70, v71
	v_mul_f32_e32 v70, 0xbfb8aa3b, v75
	v_exp_f32_e32 v70, v70
	v_mfma_f32_16x16x32_bf16 v[106:109], v[218:221], v[62:65], v[106:109]
	v_add_f32_e32 v70, 1.0, v70
	v_rcp_f32_e32 v71, v70
	v_mul_f32_e32 v70, 0xbfb8aa3b, v72
	v_exp_f32_e32 v70, v70
	v_mfma_f32_16x16x32_bf16 v[110:113], v[222:225], v[34:37], v[102:105]
	v_add_f32_e32 v70, 1.0, v70
	v_rcp_f32_e32 v70, v70
	v_mfma_f32_16x16x32_bf16 v[102:105], v[222:225], v[66:69], v[106:109]
	s_nop 4
	v_mul_f32_e32 v110, 0xbfb8aa3b, v110
	v_exp_f32_e32 v110, v110
	v_pk_mul_f32 v[70:71], v[70:71], v[72:73]
	v_add_f32_e32 v110, 1.0, v110
	v_mul_f32_e32 v70, v70, v71
	v_mul_f32_e32 v71, 0xbfb8aa3b, v76
	v_exp_f32_e32 v71, v71
	v_cvt_pk_bf16_f32 v70, v74, v70
	v_rcp_f32_e32 v183, v110
	v_mul_f32_e32 v102, 0xbfb8aa3b, v102
	v_add_f32_e32 v71, 1.0, v71
	v_rcp_f32_e32 v73, v71
	v_mul_f32_e32 v71, 0xbfb8aa3b, v78
	v_exp_f32_e32 v71, v71
	v_exp_f32_e32 v102, v102
	v_add_f32_e32 v71, 1.0, v71
	v_rcp_f32_e32 v72, v71
	v_add_f32_e32 v102, 1.0, v102
	v_pk_mul_f32 v[72:73], v[72:73], v[78:79]
	s_nop 0
	v_mul_f32_e32 v71, v72, v73
	v_mul_f32_e32 v72, 0xbfb8aa3b, v77
	v_exp_f32_e32 v72, v72
	s_nop 0
	v_add_f32_e32 v72, 1.0, v72
	v_rcp_f32_e32 v73, v72
	v_mul_f32_e32 v72, 0xbfb8aa3b, v80
	v_exp_f32_e32 v72, v72
	s_nop 0
	v_add_f32_e32 v72, 1.0, v72
	v_rcp_f32_e32 v72, v72
	s_nop 0
	v_pk_mul_f32 v[72:73], v[72:73], v[80:81]
	s_nop 0
	v_mul_f32_e32 v72, v72, v73
	v_cvt_pk_bf16_f32 v71, v71, v72
	v_lshl_add_u64 v[72:73], v[82:83], 0, v[138:139]
	global_store_dwordx2 v[72:73], v[70:71], off
	v_add_co_u32_e32 v70, vcc, s0, v116
	s_nop 1
	v_addc_co_u32_e32 v71, vcc, 0, v117, vcc
	global_load_dwordx4 v[98:101], v[70:71], off
	global_load_dwordx4 v[94:97], v[70:71], off offset:64
	global_load_dwordx4 v[90:93], v[70:71], off offset:128
	global_load_dwordx4 v[86:89], v[70:71], off offset:192
	global_load_dwordx4 v[82:85], v[70:71], off offset:256
	global_load_dwordx4 v[78:81], v[70:71], off offset:320
	global_load_dwordx4 v[74:77], v[70:71], off offset:384
	s_nop 0
	global_load_dwordx4 v[70:73], v[70:71], off offset:448
	s_nop 0
	global_load_dwordx4 v[106:109], v178, s[22:23] offset:64
	s_waitcnt vmcnt(0)
; __device__ __forceinline__ unsigned cvt_pk_bf16(float lo, float hi) { unsigned r; asm volatile("v_cvt_pk_bf16_f32 %0, %1, %2" : "=v"(r) : "v"(lo), "v"(hi)); return r; }
; __device__ __forceinline__ float bflo(unsigned w) { return __uint_as_float(w << 16); }
; __device__ __forceinline__ float bfhi(unsigned w) { return __uint_as_float(w & 0xffff0000u); }
; __device__ __forceinline__ float sigm(float x) { return __builtin_amdgcn_rcpf(1.f + __expf(-x)); }
; __device__ __forceinline__ float siluf(float x) { return x * __builtin_amdgcn_rcpf(1.f + __expf(-x)); }
; __device__ __forceinline__ float gelu_tanh(float x) { const float u = 0.7978845608028654f * (x + 0.044715f * x * x * x); return x * sigm(2.f * u); }
; #define MFMA16(a, b, c) __builtin_amdgcn_mfma_f32_16x16x32_bf16((a), (b), (c), 0, 0, 0)
; __device__ __forceinline__ void glu_task(int t, int l, const float* s5d, const bf16_t* P, const bf16_t* YB, const bf16_t* WGLU, bf16_t* Z1, int fr, int fq) {
;     ...
;     for (int c4 = 0; c4 < 4; ++c4) { f32x4 acc[2]; acc[0] = (f32x4){0.f, 0.f, 0.f, 0.f}; acc[1] = acc[0];
;         const int nrow = c4 < 3 ? (c4 + 1) * 16 : 0;
; #pragma unroll
;         for (int ks = 0; ks < 8; ++ks) wf[(c4 + 1) & 1][ks] = asfrag(ld8(wg0 + (size_t)nrow * 256 + ks * 32));
; #pragma unroll
;         for (int ks = 0; ks < 8; ++ks) { acc[0] = MFMA16(wf[c4 & 1][ks], bfr[0][ks], acc[0]); acc[1] = MFMA16(wf[c4 & 1][ks], bfr[1][ks], acc[1]); }
;         const int n4 = (cb0 + c4) * 16 + fq * 4;
;         const f32x4 dd = *(const f32x4*)(s5d + l * 256 + n4);
; #pragma unroll
;         for (int tb = 0; tb < 2; ++tb) { const u32x2 yw = eyw[tb][c4], uw = euw[tb][c4], gw = egw[tb][c4];
;             const float y0 = bflo(yw.x), y1 = bfhi(yw.x), y2 = bflo(yw.y), y3 = bfhi(yw.y), u0 = bflo(uw.x), u1 = bfhi(uw.x), u2 = bflo(uw.y), u3 = bfhi(uw.y);
;             const float g0 = gelu_tanh(y0 + dd[0] * u0), g1 = gelu_tanh(y1 + dd[1] * u1), g2 = gelu_tanh(y2 + dd[2] * u2), g3 = gelu_tanh(y3 + dd[3] * u3);
;             u32x2 w; w.x = cvt_pk_bf16(g0 * sigm(acc[tb][0]) * siluf(bflo(gw.x)), g1 * sigm(acc[tb][1]) * siluf(bfhi(gw.x)));
;             w.y = cvt_pk_bf16(g2 * sigm(acc[tb][2]) * siluf(bflo(gw.y)), g3 * sigm(acc[tb][3]) * siluf(bfhi(gw.y)));
;             *(u32x2*)(Z1 + (row0 + tb * 16) * 256 + n4) = w; } }
	v_fmac_f32_e32 v128, v107, v126
	v_mul_f32_e32 v126, 0x3d372713, v128
	v_mul_f32_e32 v126, v128, v126
	v_fma_f32 v126, v128, v126, v128
	v_mul_f32_e32 v126, 0x3f4c422a, v126
	v_add_f32_e32 v126, v126, v126
	v_mul_f32_e32 v126, 0xbfb8aa3b, v126
	v_exp_f32_e32 v126, v126
	v_fmac_f32_e32 v172, v108, v173
	v_fmac_f32_e32 v159, v106, v129
	v_fmac_f32_e32 v179, v109, v180
	v_add_f32_e32 v126, 1.0, v126
	v_rcp_f32_e32 v126, v126
	v_mul_f32_e32 v127, 0x3d372713, v159
	v_mul_f32_e32 v127, v159, v127
	v_fma_f32 v127, v159, v127, v159
	v_mul_f32_e32 v129, v128, v126
	v_mul_f32_e32 v126, 0x3d372713, v172
	v_mul_f32_e32 v126, v172, v126
	v_fma_f32 v126, v172, v126, v172
	v_mul_f32_e32 v126, 0x3f4c422a, v126
	v_add_f32_e32 v126, v126, v126
	v_mul_f32_e32 v126, 0xbfb8aa3b, v126
	v_exp_f32_e32 v126, v126
	v_and_b32_e32 v128, 0xffff0000, v124
	v_mul_f32_e32 v127, 0x3f4c422a, v127
	v_add_f32_e32 v127, v127, v127
	v_add_f32_e32 v126, 1.0, v126
	v_rcp_f32_e32 v126, v126
	v_mul_f32_e32 v127, 0xbfb8aa3b, v127
	v_exp_f32_e32 v127, v127
	v_and_b32_e32 v180, 0xffff0000, v125
	v_mul_f32_e32 v173, v172, v126
	v_mul_f32_e32 v126, 0x3d372713, v179
	v_mul_f32_e32 v126, v179, v126
	v_fma_f32 v126, v179, v126, v179
	v_mul_f32_e32 v126, 0x3f4c422a, v126
	v_add_f32_e32 v126, v126, v126
	v_mul_f32_e32 v126, 0xbfb8aa3b, v126
	v_exp_f32_e32 v126, v126
	v_add_f32_e32 v127, 1.0, v127
	v_rcp_f32_e32 v127, v127
	v_lshlrev_b32_e32 v172, 16, v125
	v_add_f32_e32 v126, 1.0, v126
	v_rcp_f32_e32 v126, v126
	v_mul_f32_e32 v127, v159, v127
	v_mul_f32_e32 v181, v179, v126
	v_lshlrev_b32_e32 v126, 16, v124
	v_mul_f32_e32 v110, 0xbfb8aa3b, v126
	v_exp_f32_e32 v110, v110
	s_nop 0
	v_add_f32_e32 v110, 1.0, v110
	v_rcp_f32_e32 v182, v110
	v_mul_f32_e32 v110, 0xbfb8aa3b, v111
	v_exp_f32_e32 v110, v110
	v_pk_mul_f32 v[126:127], v[182:183], v[126:127]
	s_nop 0
	v_mul_f32_e32 v126, v126, v127
	v_add_f32_e32 v110, 1.0, v110
	v_rcp_f32_e32 v111, v110
	v_mul_f32_e32 v110, 0xbfb8aa3b, v128
	v_exp_f32_e32 v110, v110
	s_nop 0
	v_add_f32_e32 v110, 1.0, v110
	v_rcp_f32_e32 v110, v110
	s_nop 0
	v_pk_mul_f32 v[110:111], v[110:111], v[128:129]
	s_nop 0
	v_mul_f32_e32 v110, v110, v111
	v_mul_f32_e32 v111, 0xbfb8aa3b, v112
	v_mul_f32_e32 v112, 0xbfb8aa3b, v113
	v_exp_f32_e32 v111, v111
	v_exp_f32_e32 v112, v112
	v_cvt_pk_bf16_f32 v110, v126, v110
	v_add_f32_e32 v111, 1.0, v111
	v_add_f32_e32 v112, 1.0, v112
	v_rcp_f32_e32 v127, v111
	v_mul_f32_e32 v111, 0xbfb8aa3b, v172
	v_rcp_f32_e32 v113, v112
	v_mul_f32_e32 v112, 0xbfb8aa3b, v180
	v_exp_f32_e32 v111, v111
	v_exp_f32_e32 v112, v112
	v_add_f32_e32 v111, 1.0, v111
	v_add_f32_e32 v112, 1.0, v112
	v_rcp_f32_e32 v126, v111
	v_rcp_f32_e32 v112, v112
	v_pk_mul_f32 v[126:127], v[126:127], v[172:173]
	v_pk_mul_f32 v[112:113], v[112:113], v[180:181]
	v_mul_f32_e32 v111, v126, v127
	v_mul_f32_e32 v112, v112, v113
	v_lshl_add_u64 v[172:173], s[40:41], 0, v[114:115]
	v_cvt_pk_bf16_f32 v111, v111, v112
	v_lshl_add_u64 v[112:113], v[172:173], 0, v[130:131]
	global_store_dwordx2 v[112:113], v[110:111], off
	v_lshlrev_b32_e32 v110, 16, v122
	v_lshlrev_b32_e32 v111, 16, v120
	v_fmac_f32_e32 v110, v106, v111
	v_mul_f32_e32 v106, 0x3d372713, v110
	v_mul_f32_e32 v106, v110, v106
	v_fma_f32 v106, v110, v106, v110
	v_mul_f32_e32 v106, 0x3f4c422a, v106
	v_add_f32_e32 v106, v106, v106
	v_mul_f32_e32 v106, 0xbfb8aa3b, v106
	v_exp_f32_e32 v106, v106
	v_and_b32_e32 v112, 0xffff0000, v122
	v_and_b32_e32 v115, 0xffff0000, v120
	v_fmac_f32_e32 v112, v107, v115
	v_add_f32_e32 v106, 1.0, v106
	v_rcp_f32_e32 v106, v106
	v_lshlrev_b32_e32 v113, 16, v123
	v_lshlrev_b32_e32 v120, 16, v121
	v_fmac_f32_e32 v113, v108, v120
	v_mul_f32_e32 v111, v110, v106
	v_mul_f32_e32 v106, 0x3d372713, v112
	v_mul_f32_e32 v106, v112, v106
	v_fma_f32 v106, v112, v106, v112
	v_mul_f32_e32 v106, 0x3f4c422a, v106
	v_add_f32_e32 v106, v106, v106
	v_mul_f32_e32 v106, 0xbfb8aa3b, v106
	v_exp_f32_e32 v106, v106
	v_and_b32_e32 v114, 0xffff0000, v123
	v_and_b32_e32 v121, 0xffff0000, v121
	v_fmac_f32_e32 v114, v109, v121
	v_add_f32_e32 v106, 1.0, v106
	v_rcp_f32_e32 v106, v106
	v_lshlrev_b32_e32 v110, 16, v118
	v_rcp_f32_e32 v115, v102
	v_mul_f32_e32 v102, 0xbfb8aa3b, v110
	v_mul_f32_e32 v107, v112, v106
	v_mul_f32_e32 v106, 0x3d372713, v113
	v_mul_f32_e32 v106, v113, v106
	v_fma_f32 v106, v113, v106, v113
	v_mul_f32_e32 v106, 0x3f4c422a, v106
	v_add_f32_e32 v106, v106, v106
	v_mul_f32_e32 v106, 0xbfb8aa3b, v106
	v_exp_f32_e32 v106, v106
	v_exp_f32_e32 v102, v102
	s_waitcnt lgkmcnt(0)
; __device__ __forceinline__ unsigned cvt_pk_bf16(float lo, float hi) { unsigned r; asm volatile("v_cvt_pk_bf16_f32 %0, %1, %2" : "=v"(r) : "v"(lo), "v"(hi)); return r; }
; __device__ __forceinline__ float bflo(unsigned w) { return __uint_as_float(w << 16); }
; __device__ __forceinline__ float bfhi(unsigned w) { return __uint_as_float(w & 0xffff0000u); }
; __device__ __forceinline__ float sigm(float x) { return __builtin_amdgcn_rcpf(1.f + __expf(-x)); }
; __device__ __forceinline__ float siluf(float x) { return x * __builtin_amdgcn_rcpf(1.f + __expf(-x)); }
; __device__ __forceinline__ float gelu_tanh(float x) { const float u = 0.7978845608028654f * (x + 0.044715f * x * x * x); return x * sigm(2.f * u); }
; #define MFMA16(a, b, c) __builtin_amdgcn_mfma_f32_16x16x32_bf16((a), (b), (c), 0, 0, 0)
; __device__ __forceinline__ void glu_task(int t, int l, const float* s5d, const bf16_t* P, const bf16_t* YB, const bf16_t* WGLU, bf16_t* Z1, int fr, int fq) {
;     ...
;     for (int c4 = 0; c4 < 4; ++c4) { f32x4 acc[2]; acc[0] = (f32x4){0.f, 0.f, 0.f, 0.f}; acc[1] = acc[0];
;         const int nrow = c4 < 3 ? (c4 + 1) * 16 : 0;
; #pragma unroll
;         for (int ks = 0; ks < 8; ++ks) wf[(c4 + 1) & 1][ks] = asfrag(ld8(wg0 + (size_t)nrow * 256 + ks * 32));
; #pragma unroll
;         for (int ks = 0; ks < 8; ++ks) { acc[0] = MFMA16(wf[c4 & 1][ks], bfr[0][ks], acc[0]); acc[1] = MFMA16(wf[c4 & 1][ks], bfr[1][ks], acc[1]); }
;         const int n4 = (cb0 + c4) * 16 + fq * 4;
;         const f32x4 dd = *(const f32x4*)(s5d + l * 256 + n4);
; #pragma unroll
;         for (int tb = 0; tb < 2; ++tb) { const u32x2 yw = eyw[tb][c4], uw = euw[tb][c4], gw = egw[tb][c4];
;             const float y0 = bflo(yw.x), y1 = bfhi(yw.x), y2 = bflo(yw.y), y3 = bfhi(yw.y), u0 = bflo(uw.x), u1 = bfhi(uw.x), u2 = bflo(uw.y), u3 = bfhi(uw.y);
;             const float g0 = gelu_tanh(y0 + dd[0] * u0), g1 = gelu_tanh(y1 + dd[1] * u1), g2 = gelu_tanh(y2 + dd[2] * u2), g3 = gelu_tanh(y3 + dd[3] * u3);
;             u32x2 w; w.x = cvt_pk_bf16(g0 * sigm(acc[tb][0]) * siluf(bflo(gw.x)), g1 * sigm(acc[tb][1]) * siluf(bfhi(gw.x)));
;             w.y = cvt_pk_bf16(g2 * sigm(acc[tb][2]) * siluf(bflo(gw.y)), g3 * sigm(acc[tb][3]) * siluf(bfhi(gw.y)));
;             *(u32x2*)(Z1 + (row0 + tb * 16) * 256 + n4) = w; } }
	v_mfma_f32_16x16x32_bf16 v[180:183], v[98:101], v[2:5], 0
	v_lshlrev_b32_e32 v112, 16, v119
	v_add_f32_e32 v106, 1.0, v106
	v_rcp_f32_e32 v106, v106
	v_add_f32_e32 v102, 1.0, v102
	v_mfma_f32_16x16x32_bf16 v[98:101], v[98:101], v[38:41], 0
	v_mul_f32_e32 v113, v113, v106
	v_mul_f32_e32 v106, 0x3d372713, v114
	v_mul_f32_e32 v106, v114, v106
	v_fma_f32 v106, v114, v106, v114
	v_mul_f32_e32 v106, 0x3f4c422a, v106
	v_add_f32_e32 v106, v106, v106
	v_mul_f32_e32 v106, 0xbfb8aa3b, v106
	v_exp_f32_e32 v106, v106
	v_mfma_f32_16x16x32_bf16 v[180:183], v[94:97], v[6:9], v[180:183]
	v_add_f32_e32 v106, 1.0, v106
	v_rcp_f32_e32 v106, v106
	v_mfma_f32_16x16x32_bf16 v[94:97], v[94:97], v[42:45], v[98:101]
	v_mul_f32_e32 v109, v114, v106
	v_rcp_f32_e32 v114, v102
	v_mul_f32_e32 v102, 0xbfb8aa3b, v103
	v_exp_f32_e32 v102, v102
	v_and_b32_e32 v106, 0xffff0000, v118
	v_mfma_f32_16x16x32_bf16 v[98:101], v[90:93], v[14:17], v[180:183]
	v_mul_f32_e64 v110, v114, v110
	v_mul_f32_e64 v111, v115, v111
	v_add_f32_e32 v102, 1.0, v102
	v_rcp_f32_e32 v103, v102
	v_mul_f32_e32 v102, 0xbfb8aa3b, v106
	v_exp_f32_e32 v102, v102
	v_mfma_f32_16x16x32_bf16 v[90:93], v[90:93], v[46:49], v[94:97]
	v_mul_f32_e32 v108, v110, v111
	v_add_f32_e32 v102, 1.0, v102
	v_rcp_f32_e32 v102, v102
	v_mfma_f32_16x16x32_bf16 v[94:97], v[86:89], v[18:21], v[98:101]
	v_mul_f32_e64 v102, v102, v106
	v_mul_f32_e64 v103, v103, v107
	v_mul_f32_e32 v102, v102, v103
	v_mul_f32_e32 v103, 0xbfb8aa3b, v104
	v_mul_f32_e32 v104, 0xbfb8aa3b, v105
	v_exp_f32_e32 v103, v103
	v_exp_f32_e32 v104, v104
	v_cvt_pk_bf16_f32 v102, v108, v102
	v_and_b32_e32 v108, 0xffff0000, v119
	v_add_f32_e32 v103, 1.0, v103
	v_add_f32_e32 v104, 1.0, v104
	v_mfma_f32_16x16x32_bf16 v[86:89], v[86:89], v[50:53], v[90:93]
	v_rcp_f32_e32 v107, v103
	v_mul_f32_e32 v103, 0xbfb8aa3b, v112
	v_rcp_f32_e32 v105, v104
	v_mul_f32_e32 v104, 0xbfb8aa3b, v108
	v_exp_f32_e32 v103, v103
	v_exp_f32_e32 v104, v104
	v_mfma_f32_16x16x32_bf16 v[90:93], v[82:85], v[22:25], v[94:97]
	v_add_f32_e32 v103, 1.0, v103
	v_add_f32_e32 v104, 1.0, v104
	v_mfma_f32_16x16x32_bf16 v[82:85], v[82:85], v[54:57], v[86:89]
	v_rcp_f32_e32 v106, v103
	v_rcp_f32_e32 v104, v104
	v_pk_mul_f32 v[106:107], v[106:107], v[112:113]
	v_mfma_f32_16x16x32_bf16 v[86:89], v[78:81], v[26:29], v[90:93]
	v_mul_f32_e64 v104, v104, v108
	v_mul_f32_e64 v105, v105, v109
	v_mul_f32_e32 v103, v106, v107
	v_mul_f32_e32 v104, v104, v105
	v_mfma_f32_16x16x32_bf16 v[78:81], v[78:81], v[58:61], v[82:85]
	v_cvt_pk_bf16_f32 v103, v103, v104
	v_lshl_add_u64 v[104:105], v[132:133], 0, v[138:139]
	global_store_dwordx2 v[104:105], v[102:103], off
	v_mfma_f32_16x16x32_bf16 v[82:85], v[74:77], v[30:33], v[86:89]
	v_add_co_u32_e32 v102, vcc, s18, v116
	v_lshlrev_b32_e32 v90, 16, v171
	v_mfma_f32_16x16x32_bf16 v[74:77], v[74:77], v[62:65], v[78:81]
	v_addc_co_u32_e32 v103, vcc, 0, v117, vcc
	global_load_dwordx4 v[130:133], v[102:103], off
	global_load_dwordx4 v[126:129], v[102:103], off offset:64
	global_load_dwordx4 v[122:125], v[102:103], off offset:128
	global_load_dwordx4 v[118:121], v[102:103], off offset:192
	global_load_dwordx4 v[114:117], v[102:103], off offset:256
	global_load_dwordx4 v[110:113], v[102:103], off offset:320
	global_load_dwordx4 v[106:109], v[102:103], off offset:384
	s_nop 0
	global_load_dwordx4 v[102:105], v[102:103], off offset:448
	v_mfma_f32_16x16x32_bf16 v[78:81], v[70:73], v[34:37], v[82:85]
	v_lshlrev_b32_e32 v86, 16, v170
	v_lshlrev_b32_e32 v87, 16, v168
	v_and_b32_e32 v88, 0xffff0000, v170
	v_mfma_f32_16x16x32_bf16 v[70:73], v[70:73], v[66:69], v[74:77]
	v_and_b32_e32 v89, 0xffff0000, v168
	v_lshlrev_b32_e32 v91, 16, v169
	v_and_b32_e32 v92, 0xffff0000, v171
	global_load_dwordx4 v[74:77], v178, s[22:23] offset:128
	v_and_b32_e32 v93, 0xffff0000, v169
	v_mul_f32_e32 v78, 0xbfb8aa3b, v78
	v_exp_f32_e32 v78, v78
	v_or_b32_e32 v82, 64, v158
	v_mov_b32_e32 v83, v1
	v_lshl_add_u64 v[84:85], s[40:41], 0, v[82:83]
	v_add_f32_e32 v78, 1.0, v78
	v_rcp_f32_e32 v95, v78
	v_mul_f32_e32 v70, 0xbfb8aa3b, v70
	v_exp_f32_e32 v70, v70
	s_waitcnt vmcnt(0) lgkmcnt(0)
	v_mfma_f32_16x16x32_bf16 v[2:5], v[130:133], v[2:5], 0
	v_add_f32_e32 v70, 1.0, v70
	v_subrev_co_u32_e32 v177, vcc, 1, v177
	v_mfma_f32_16x16x32_bf16 v[38:41], v[130:133], v[38:41], 0
	s_and_b64 s[6:7], s[42:43], vcc
	s_and_b64 s[6:7], s[6:7], exec
	s_cselect_b32 s5, s4, s19
	v_mfma_f32_16x16x32_bf16 v[2:5], v[126:129], v[6:9], v[2:5]
	s_and_b64 s[6:7], s[14:15], exec
	s_cselect_b32 s20, s5, s1
	s_cmp_ge_i32 s20, s19
	v_mfma_f32_16x16x32_bf16 v[6:9], v[126:129], v[42:45], v[38:41]
	v_fmac_f32_e32 v86, v74, v87
	v_mul_f32_e32 v87, 0x3d372713, v86
	v_mul_f32_e32 v87, v86, v87
	v_fma_f32 v87, v86, v87, v86
	v_mul_f32_e32 v87, 0x3f4c422a, v87
	v_add_f32_e32 v87, v87, v87
	v_mul_f32_e32 v87, 0xbfb8aa3b, v87
	v_exp_f32_e32 v87, v87
	v_fmac_f32_e32 v88, v75, v89
	v_fmac_f32_e32 v90, v76, v91
	v_fmac_f32_e32 v92, v77, v93
	v_add_f32_e32 v87, 1.0, v87
	v_rcp_f32_e32 v87, v87
	v_mfma_f32_16x16x32_bf16 v[2:5], v[122:125], v[14:17], v[2:5]
	v_mul_f32_e32 v87, v86, v87
	v_mul_f32_e32 v86, 0x3d372713, v88
	v_mul_f32_e32 v86, v88, v86
	v_fma_f32 v86, v88, v86, v88
	v_mul_f32_e32 v86, 0x3f4c422a, v86
	v_add_f32_e32 v86, v86, v86
	v_mul_f32_e32 v86, 0xbfb8aa3b, v86
	v_exp_f32_e32 v86, v86
	v_mfma_f32_16x16x32_bf16 v[6:9], v[122:125], v[46:49], v[6:9]
	v_add_f32_e32 v86, 1.0, v86
	v_rcp_f32_e32 v86, v86
	v_mfma_f32_16x16x32_bf16 v[2:5], v[118:121], v[18:21], v[2:5]
	v_or_b32_e32 v18, 0x60, v158
	v_mov_b32_e32 v19, v1
	v_mul_f32_e32 v89, v88, v86
	v_mul_f32_e32 v86, 0x3d372713, v90
	v_mul_f32_e32 v86, v90, v86
	v_fma_f32 v86, v90, v86, v90
; __device__ __forceinline__ unsigned cvt_pk_bf16(float lo, float hi) { unsigned r; asm volatile("v_cvt_pk_bf16_f32 %0, %1, %2" : "=v"(r) : "v"(lo), "v"(hi)); return r; }
; __device__ __forceinline__ float bflo(unsigned w) { return __uint_as_float(w << 16); }
; __device__ __forceinline__ float bfhi(unsigned w) { return __uint_as_float(w & 0xffff0000u); }
; __device__ __forceinline__ float sigm(float x) { return __builtin_amdgcn_rcpf(1.f + __expf(-x)); }
; __device__ __forceinline__ float siluf(float x) { return x * __builtin_amdgcn_rcpf(1.f + __expf(-x)); }
; __device__ __forceinline__ float gelu_tanh(float x) { const float u = 0.7978845608028654f * (x + 0.044715f * x * x * x); return x * sigm(2.f * u); }
; #define MFMA16(a, b, c) __builtin_amdgcn_mfma_f32_16x16x32_bf16((a), (b), (c), 0, 0, 0)
; __device__ __forceinline__ void glu_task(int t, int l, const float* s5d, const bf16_t* P, const bf16_t* YB, const bf16_t* WGLU, bf16_t* Z1, int fr, int fq) {
;     ...
;     for (int c4 = 0; c4 < 4; ++c4) { f32x4 acc[2]; acc[0] = (f32x4){0.f, 0.f, 0.f, 0.f}; acc[1] = acc[0];
;         const int nrow = c4 < 3 ? (c4 + 1) * 16 : 0;
; #pragma unroll
;         for (int ks = 0; ks < 8; ++ks) wf[(c4 + 1) & 1][ks] = asfrag(ld8(wg0 + (size_t)nrow * 256 + ks * 32));
; #pragma unroll
;         for (int ks = 0; ks < 8; ++ks) { acc[0] = MFMA16(wf[c4 & 1][ks], bfr[0][ks], acc[0]); acc[1] = MFMA16(wf[c4 & 1][ks], bfr[1][ks], acc[1]); }
;         const int n4 = (cb0 + c4) * 16 + fq * 4;
;         const f32x4 dd = *(const f32x4*)(s5d + l * 256 + n4);
; #pragma unroll
;         for (int tb = 0; tb < 2; ++tb) { const u32x2 yw = eyw[tb][c4], uw = euw[tb][c4], gw = egw[tb][c4];
;             const float y0 = bflo(yw.x), y1 = bfhi(yw.x), y2 = bflo(yw.y), y3 = bfhi(yw.y), u0 = bflo(uw.x), u1 = bfhi(uw.x), u2 = bflo(uw.y), u3 = bfhi(uw.y);
;             const float g0 = gelu_tanh(y0 + dd[0] * u0), g1 = gelu_tanh(y1 + dd[1] * u1), g2 = gelu_tanh(y2 + dd[2] * u2), g3 = gelu_tanh(y3 + dd[3] * u3);
;             u32x2 w; w.x = cvt_pk_bf16(g0 * sigm(acc[tb][0]) * siluf(bflo(gw.x)), g1 * sigm(acc[tb][1]) * siluf(bfhi(gw.x)));
;             w.y = cvt_pk_bf16(g2 * sigm(acc[tb][2]) * siluf(bflo(gw.y)), g3 * sigm(acc[tb][3]) * siluf(bfhi(gw.y)));
;             *(u32x2*)(Z1 + (row0 + tb * 16) * 256 + n4) = w; } }
	v_mul_f32_e32 v86, 0x3f4c422a, v86
	v_add_f32_e32 v86, v86, v86
	v_mul_f32_e32 v86, 0xbfb8aa3b, v86
	v_exp_f32_e32 v86, v86
	v_and_b32_e32 v88, 0xffff0000, v166
	v_mfma_f32_16x16x32_bf16 v[6:9], v[118:121], v[50:53], v[6:9]
	v_lshl_add_u64 v[20:21], s[40:41], 0, v[18:19]
	v_add_f32_e32 v86, 1.0, v86
	v_rcp_f32_e32 v86, v86
	v_mfma_f32_16x16x32_bf16 v[2:5], v[114:117], v[22:25], v[2:5]
	v_lshlrev_b32_e32 v22, 16, v156
	v_lshlrev_b32_e32 v23, 16, v148
	v_mul_f32_e32 v91, v90, v86
	v_mul_f32_e32 v86, 0x3d372713, v92
	v_mul_f32_e32 v86, v92, v86
	v_fma_f32 v86, v92, v86, v92
	v_mul_f32_e32 v86, 0x3f4c422a, v86
	v_add_f32_e32 v86, v86, v86
	v_mul_f32_e32 v86, 0xbfb8aa3b, v86
	v_exp_f32_e32 v86, v86
	v_lshlrev_b32_e32 v90, 16, v167
	v_mfma_f32_16x16x32_bf16 v[6:9], v[114:117], v[54:57], v[6:9]
	v_and_b32_e32 v24, 0xffff0000, v156
	v_add_f32_e32 v86, 1.0, v86
	v_rcp_f32_e32 v86, v86
	v_mfma_f32_16x16x32_bf16 v[2:5], v[110:113], v[26:29], v[2:5]
	v_and_b32_e32 v25, 0xffff0000, v148
	v_lshlrev_b32_e32 v26, 16, v157
	v_mul_f32_e32 v93, v92, v86
	v_lshlrev_b32_e32 v86, 16, v166
	v_mul_f32_e32 v78, 0xbfb8aa3b, v86
	v_exp_f32_e32 v78, v78
	v_and_b32_e32 v92, 0xffff0000, v167
	v_mfma_f32_16x16x32_bf16 v[6:9], v[110:113], v[58:61], v[6:9]
	v_lshlrev_b32_e32 v27, 16, v149
	v_add_f32_e32 v78, 1.0, v78
	v_rcp_f32_e32 v94, v78
	v_mul_f32_e32 v78, 0xbfb8aa3b, v79
	v_exp_f32_e32 v78, v78
	v_mfma_f32_16x16x32_bf16 v[2:5], v[106:109], v[30:33], v[2:5]
	v_mul_f32_e64 v86, v94, v86
	v_mul_f32_e64 v87, v95, v87
	v_and_b32_e32 v28, 0xffff0000, v157
	v_add_f32_e32 v78, 1.0, v78
	v_rcp_f32_e32 v79, v78
	v_mul_f32_e32 v78, 0xbfb8aa3b, v88
	v_exp_f32_e32 v78, v78
	v_mul_f32_e32 v86, v86, v87
	v_mfma_f32_16x16x32_bf16 v[6:9], v[106:109], v[62:65], v[6:9]
	v_and_b32_e32 v29, 0xffff0000, v149
	v_add_f32_e32 v78, 1.0, v78
	v_rcp_f32_e32 v78, v78
	v_mfma_f32_16x16x32_bf16 v[14:17], v[102:105], v[34:37], v[2:5]
	v_mul_f32_e64 v78, v78, v88
	v_mul_f32_e64 v79, v79, v89
	v_mul_f32_e32 v78, v78, v79
	v_mul_f32_e32 v79, 0xbfb8aa3b, v80
	v_mul_f32_e32 v80, 0xbfb8aa3b, v81
	v_exp_f32_e32 v79, v79
	v_exp_f32_e32 v80, v80
	v_cvt_pk_bf16_f32 v78, v86, v78
	v_mfma_f32_16x16x32_bf16 v[2:5], v[102:105], v[66:69], v[6:9]
	v_add_f32_e32 v79, 1.0, v79
	v_add_f32_e32 v80, 1.0, v80
	v_rcp_f32_e32 v87, v79
	v_mul_f32_e32 v79, 0xbfb8aa3b, v90
	v_rcp_f32_e32 v81, v80
	v_mul_f32_e32 v80, 0xbfb8aa3b, v92
	v_exp_f32_e32 v79, v79
	v_exp_f32_e32 v80, v80
	v_mul_f32_e32 v14, 0xbfb8aa3b, v14
	v_exp_f32_e32 v14, v14
	v_add_f32_e32 v79, 1.0, v79
	v_add_f32_e32 v80, 1.0, v80
	v_rcp_f32_e32 v86, v79
	v_rcp_f32_e32 v80, v80
	v_add_f32_e32 v14, 1.0, v14
	v_rcp_f32_e32 v31, v14
	v_pk_mul_f32 v[86:87], v[86:87], v[90:91]
	v_pk_mul_f32 v[80:81], v[80:81], v[92:93]
	v_mul_f32_e32 v79, v86, v87
	v_mul_f32_e32 v80, v80, v81
	v_cvt_pk_bf16_f32 v79, v79, v80
	v_lshl_add_u64 v[80:81], v[172:173], 0, v[82:83]
	global_store_dwordx2 v[80:81], v[78:79], off
	v_lshlrev_b32_e32 v78, 16, v164
	v_lshlrev_b32_e32 v79, 16, v162
	v_fmac_f32_e32 v78, v74, v79
	v_mul_f32_e32 v74, 0x3d372713, v78
	v_mul_f32_e32 v74, v78, v74
	v_fma_f32 v74, v78, v74, v78
	v_mul_f32_e32 v74, 0x3f4c422a, v74
	v_add_f32_e32 v74, v74, v74
	v_mul_f32_e32 v74, 0xbfb8aa3b, v74
	v_exp_f32_e32 v74, v74
	v_and_b32_e32 v80, 0xffff0000, v164
	v_and_b32_e32 v83, 0xffff0000, v162
	v_fmac_f32_e32 v80, v75, v83
	v_add_f32_e32 v74, 1.0, v74
	v_rcp_f32_e32 v74, v74
	v_lshlrev_b32_e32 v81, 16, v165
	v_lshlrev_b32_e32 v86, 16, v163
	v_fmac_f32_e32 v81, v76, v86
	v_mul_f32_e32 v79, v78, v74
	v_mul_f32_e32 v74, 0x3d372713, v80
	v_mul_f32_e32 v74, v80, v74
	v_fma_f32 v74, v80, v74, v80
	v_mul_f32_e32 v74, 0x3f4c422a, v74
	v_add_f32_e32 v74, v74, v74
	v_mul_f32_e32 v74, 0xbfb8aa3b, v74
	v_exp_f32_e32 v74, v74
	v_and_b32_e32 v82, 0xffff0000, v165
	v_and_b32_e32 v87, 0xffff0000, v163
	v_fmac_f32_e32 v82, v77, v87
	v_add_f32_e32 v74, 1.0, v74
	v_rcp_f32_e32 v74, v74
	v_lshlrev_b32_e32 v78, 16, v160
	v_rcp_f32_e32 v83, v70
	v_mul_f32_e32 v70, 0xbfb8aa3b, v78
	v_mul_f32_e32 v75, v80, v74
	v_mul_f32_e32 v74, 0x3d372713, v81
	v_mul_f32_e32 v74, v81, v74
	v_fma_f32 v74, v81, v74, v81
	v_mul_f32_e32 v74, 0x3f4c422a, v74
	v_add_f32_e32 v74, v74, v74
	v_mul_f32_e32 v74, 0xbfb8aa3b, v74
	v_exp_f32_e32 v74, v74
	v_exp_f32_e32 v70, v70
	v_lshlrev_b32_e32 v80, 16, v161
	v_mul_f32_e32 v2, 0xbfb8aa3b, v2
	v_add_f32_e32 v74, 1.0, v74
	v_rcp_f32_e32 v74, v74
	v_add_f32_e32 v70, 1.0, v70
	v_exp_f32_e32 v2, v2
	v_mul_f32_e32 v81, v81, v74
	v_mul_f32_e32 v74, 0x3d372713, v82
	v_mul_f32_e32 v74, v82, v74
	v_fma_f32 v74, v82, v74, v82
	v_mul_f32_e32 v74, 0x3f4c422a, v74
	v_add_f32_e32 v74, v74, v74
	v_mul_f32_e32 v74, 0xbfb8aa3b, v74
	v_exp_f32_e32 v74, v74
	v_add_f32_e32 v2, 1.0, v2
	v_add_f32_e32 v74, 1.0, v74
	v_rcp_f32_e32 v74, v74
	s_nop 0
	v_mul_f32_e32 v77, v82, v74
	v_rcp_f32_e32 v82, v70
	v_mul_f32_e32 v70, 0xbfb8aa3b, v71
	v_exp_f32_e32 v70, v70
	v_and_b32_e32 v74, 0xffff0000, v160
	v_pk_mul_f32 v[78:79], v[82:83], v[78:79]
	v_add_f32_e32 v70, 1.0, v70
	v_rcp_f32_e32 v71, v70
	v_mul_f32_e32 v70, 0xbfb8aa3b, v74
	v_exp_f32_e32 v70, v70
	v_mul_f32_e32 v76, v78, v79
	v_add_f32_e32 v70, 1.0, v70
	v_rcp_f32_e32 v70, v70
	s_nop 0
	v_pk_mul_f32 v[70:71], v[70:71], v[74:75]
	s_nop 0
	v_mul_f32_e32 v70, v70, v71
	v_mul_f32_e32 v71, 0xbfb8aa3b, v72
	v_mul_f32_e32 v72, 0xbfb8aa3b, v73
	v_exp_f32_e32 v71, v71
	v_exp_f32_e32 v72, v72
	v_cvt_pk_bf16_f32 v70, v76, v70
	v_and_b32_e32 v76, 0xffff0000, v161
	v_add_f32_e32 v71, 1.0, v71
	v_add_f32_e32 v72, 1.0, v72
	v_rcp_f32_e32 v75, v71
	v_mul_f32_e32 v71, 0xbfb8aa3b, v80
	v_rcp_f32_e32 v73, v72
	v_mul_f32_e32 v72, 0xbfb8aa3b, v76
	v_exp_f32_e32 v71, v71
	v_exp_f32_e32 v72, v72
	v_add_f32_e32 v71, 1.0, v71
	v_add_f32_e32 v72, 1.0, v72
	v_rcp_f32_e32 v74, v71
	v_rcp_f32_e32 v72, v72
	v_pk_mul_f32 v[74:75], v[74:75], v[80:81]
	v_pk_mul_f32 v[72:73], v[72:73], v[76:77]
	v_mul_f32_e32 v71, v74, v75
	v_mul_f32_e32 v72, v72, v73
	v_cvt_pk_bf16_f32 v71, v71, v72
	v_lshl_add_u64 v[72:73], v[84:85], 0, v[138:139]
	global_store_dwordx2 v[72:73], v[70:71], off
	global_load_dwordx4 v[6:9], v178, s[22:23] offset:192
	s_waitcnt vmcnt(0)
; __device__ __forceinline__ unsigned cvt_pk_bf16(float lo, float hi) { unsigned r; asm volatile("v_cvt_pk_bf16_f32 %0, %1, %2" : "=v"(r) : "v"(lo), "v"(hi)); return r; }
; __device__ __forceinline__ float bflo(unsigned w) { return __uint_as_float(w << 16); }
; __device__ __forceinline__ float bfhi(unsigned w) { return __uint_as_float(w & 0xffff0000u); }
; __device__ __forceinline__ float sigm(float x) { return __builtin_amdgcn_rcpf(1.f + __expf(-x)); }
; __device__ __forceinline__ float siluf(float x) { return x * __builtin_amdgcn_rcpf(1.f + __expf(-x)); }
; __device__ __forceinline__ void glu_task(int t, int l, const float* s5d, const bf16_t* P, const bf16_t* YB, const bf16_t* WGLU, bf16_t* Z1, int fr, int fq) {
;     ...
;     for (int c4 = 0; c4 < 4; ++c4) { f32x4 acc[2]; acc[0] = (f32x4){0.f, 0.f, 0.f, 0.f}; acc[1] = acc[0];
;         const int nrow = c4 < 3 ? (c4 + 1) * 16 : 0;
; #pragma unroll
;         for (int ks = 0; ks < 8; ++ks) wf[(c4 + 1) & 1][ks] = asfrag(ld8(wg0 + (size_t)nrow * 256 + ks * 32));
; #pragma unroll
;         for (int ks = 0; ks < 8; ++ks) { acc[0] = MFMA16(wf[c4 & 1][ks], bfr[0][ks], acc[0]); acc[1] = MFMA16(wf[c4 & 1][ks], bfr[1][ks], acc[1]); }
;         const int n4 = (cb0 + c4) * 16 + fq * 4;
;         const f32x4 dd = *(const f32x4*)(s5d + l * 256 + n4);
; #pragma unroll
;         for (int tb = 0; tb < 2; ++tb) { const u32x2 yw = eyw[tb][c4], uw = euw[tb][c4], gw = egw[tb][c4];
;             const float y0 = bflo(yw.x), y1 = bfhi(yw.x), y2 = bflo(yw.y), y3 = bfhi(yw.y), u0 = bflo(uw.x), u1 = bfhi(uw.x), u2 = bflo(uw.y), u3 = bfhi(uw.y);
;             const float g0 = gelu_tanh(y0 + dd[0] * u0), g1 = gelu_tanh(y1 + dd[1] * u1), g2 = gelu_tanh(y2 + dd[2] * u2), g3 = gelu_tanh(y3 + dd[3] * u3);
;             u32x2 w; w.x = cvt_pk_bf16(g0 * sigm(acc[tb][0]) * siluf(bflo(gw.x)), g1 * sigm(acc[tb][1]) * siluf(bfhi(gw.x)));
;             w.y = cvt_pk_bf16(g2 * sigm(acc[tb][2]) * siluf(bflo(gw.y)), g3 * sigm(acc[tb][3]) * siluf(bfhi(gw.y)));
;             *(u32x2*)(Z1 + (row0 + tb * 16) * 256 + n4) = w; } }
; __global__ void __launch_bounds__(512, 2) fwd_kernel(KArgs a) {
;     ...
;             { IDS; for (int t = gw, k_ = 0; t < (wctx ? MH : ML) / 8; t = NGW != 2048 ? t + NGW : (((gw & 7) == 0 && k_ == 0) ? NGW + (gw >> 3) : (wctx ? MH : ML) / 8), ++k_) glu_task(t, l, a.in[21], P, YB, WGLU, Z1, fr, fq); }
	v_fmac_f32_e32 v22, v6, v23
	v_mul_f32_e32 v23, 0x3d372713, v22
	v_mul_f32_e32 v23, v22, v23
	v_fma_f32 v23, v22, v23, v22
	v_mul_f32_e32 v23, 0x3f4c422a, v23
	v_add_f32_e32 v23, v23, v23
	v_mul_f32_e32 v23, 0xbfb8aa3b, v23
	v_exp_f32_e32 v23, v23
	v_fmac_f32_e32 v24, v7, v25
	v_fmac_f32_e32 v26, v8, v27
	v_fmac_f32_e32 v28, v9, v29
	v_add_f32_e32 v23, 1.0, v23
	v_rcp_f32_e32 v23, v23
	s_nop 0
	v_mul_f32_e32 v23, v22, v23
	v_mul_f32_e32 v22, 0x3d372713, v24
	v_mul_f32_e32 v22, v24, v22
	v_fma_f32 v22, v24, v22, v24
	v_mul_f32_e32 v22, 0x3f4c422a, v22
	v_add_f32_e32 v22, v22, v22
	v_mul_f32_e32 v22, 0xbfb8aa3b, v22
	v_exp_f32_e32 v22, v22
	s_nop 0
	v_add_f32_e32 v22, 1.0, v22
	v_rcp_f32_e32 v22, v22
	s_nop 0
	v_mul_f32_e32 v25, v24, v22
	v_mul_f32_e32 v22, 0x3d372713, v26
	v_mul_f32_e32 v22, v26, v22
	v_fma_f32 v22, v26, v22, v26
	v_mul_f32_e32 v22, 0x3f4c422a, v22
	v_add_f32_e32 v22, v22, v22
	v_mul_f32_e32 v22, 0xbfb8aa3b, v22
	v_exp_f32_e32 v22, v22
	v_and_b32_e32 v24, 0xffff0000, v146
	v_add_f32_e32 v22, 1.0, v22
	v_rcp_f32_e32 v22, v22
	s_nop 0
	v_mul_f32_e32 v27, v26, v22
	v_mul_f32_e32 v22, 0x3d372713, v28
	v_mul_f32_e32 v22, v28, v22
	v_fma_f32 v22, v28, v22, v28
	v_mul_f32_e32 v22, 0x3f4c422a, v22
	v_add_f32_e32 v22, v22, v22
	v_mul_f32_e32 v22, 0xbfb8aa3b, v22
	v_exp_f32_e32 v22, v22
	v_lshlrev_b32_e32 v26, 16, v147
	v_add_f32_e32 v22, 1.0, v22
	v_rcp_f32_e32 v22, v22
	s_nop 0
	v_mul_f32_e32 v29, v28, v22
	v_lshlrev_b32_e32 v22, 16, v146
	v_mul_f32_e32 v14, 0xbfb8aa3b, v22
	v_exp_f32_e32 v14, v14
	v_and_b32_e32 v28, 0xffff0000, v147
	v_add_f32_e32 v14, 1.0, v14
	v_rcp_f32_e32 v30, v14
	v_mul_f32_e32 v14, 0xbfb8aa3b, v15
	v_exp_f32_e32 v14, v14
	v_pk_mul_f32 v[22:23], v[30:31], v[22:23]
	s_nop 0
	v_mul_f32_e32 v22, v22, v23
	v_add_f32_e32 v14, 1.0, v14
	v_rcp_f32_e32 v15, v14
	v_mul_f32_e32 v14, 0xbfb8aa3b, v24
	v_exp_f32_e32 v14, v14
	s_nop 0
	v_add_f32_e32 v14, 1.0, v14
	v_rcp_f32_e32 v14, v14
	s_nop 0
	v_pk_mul_f32 v[14:15], v[14:15], v[24:25]
	s_nop 0
	v_mul_f32_e32 v14, v14, v15
	v_mul_f32_e32 v15, 0xbfb8aa3b, v16
	v_mul_f32_e32 v16, 0xbfb8aa3b, v17
	v_exp_f32_e32 v15, v15
	v_exp_f32_e32 v16, v16
	v_cvt_pk_bf16_f32 v14, v22, v14
	v_add_f32_e32 v15, 1.0, v15
	v_add_f32_e32 v16, 1.0, v16
	v_rcp_f32_e32 v23, v15
	v_mul_f32_e32 v15, 0xbfb8aa3b, v26
	v_rcp_f32_e32 v17, v16
	v_mul_f32_e32 v16, 0xbfb8aa3b, v28
	v_exp_f32_e32 v15, v15
	v_exp_f32_e32 v16, v16
	v_add_f32_e32 v15, 1.0, v15
	v_add_f32_e32 v16, 1.0, v16
	v_rcp_f32_e32 v22, v15
	v_rcp_f32_e32 v16, v16
	v_pk_mul_f32 v[22:23], v[22:23], v[26:27]
	v_pk_mul_f32 v[16:17], v[16:17], v[28:29]
	v_mul_f32_e32 v15, v22, v23
	v_mul_f32_e32 v16, v16, v17
	v_cvt_pk_bf16_f32 v15, v15, v16
	v_lshl_add_u64 v[16:17], v[172:173], 0, v[18:19]
	global_store_dwordx2 v[16:17], v[14:15], off
	v_lshlrev_b32_e32 v14, 16, v144
	v_lshlrev_b32_e32 v15, 16, v142
	v_fmac_f32_e32 v14, v6, v15
	v_mul_f32_e32 v6, 0x3d372713, v14
	v_mul_f32_e32 v6, v14, v6
	v_fma_f32 v6, v14, v6, v14
	v_mul_f32_e32 v6, 0x3f4c422a, v6
	v_add_f32_e32 v6, v6, v6
	v_mul_f32_e32 v6, 0xbfb8aa3b, v6
	v_exp_f32_e32 v6, v6
	v_and_b32_e32 v16, 0xffff0000, v144
	v_and_b32_e32 v19, 0xffff0000, v142
	v_fmac_f32_e32 v16, v7, v19
	v_add_f32_e32 v6, 1.0, v6
	v_rcp_f32_e32 v6, v6
	v_lshlrev_b32_e32 v17, 16, v145
	v_lshlrev_b32_e32 v22, 16, v143
	v_fmac_f32_e32 v17, v8, v22
	v_mul_f32_e32 v15, v14, v6
	v_mul_f32_e32 v6, 0x3d372713, v16
	v_mul_f32_e32 v6, v16, v6
	v_fma_f32 v6, v16, v6, v16
	v_mul_f32_e32 v6, 0x3f4c422a, v6
	v_add_f32_e32 v6, v6, v6
	v_mul_f32_e32 v6, 0xbfb8aa3b, v6
	v_exp_f32_e32 v6, v6
	v_and_b32_e32 v18, 0xffff0000, v145
	v_and_b32_e32 v23, 0xffff0000, v143
	v_fmac_f32_e32 v18, v9, v23
	v_add_f32_e32 v6, 1.0, v6
	v_rcp_f32_e32 v6, v6
	v_lshlrev_b32_e32 v14, 16, v140
	v_rcp_f32_e32 v19, v2
	v_mul_f32_e32 v2, 0xbfb8aa3b, v14
	v_mul_f32_e32 v7, v16, v6
	v_mul_f32_e32 v6, 0x3d372713, v17
	v_mul_f32_e32 v6, v17, v6
	v_fma_f32 v6, v17, v6, v17
	v_mul_f32_e32 v6, 0x3f4c422a, v6
	v_add_f32_e32 v6, v6, v6
	v_mul_f32_e32 v6, 0xbfb8aa3b, v6
	v_exp_f32_e32 v6, v6
	v_exp_f32_e32 v2, v2
	v_lshlrev_b32_e32 v16, 16, v141
	v_add_f32_e32 v6, 1.0, v6
	v_rcp_f32_e32 v6, v6
	v_add_f32_e32 v2, 1.0, v2
	v_mul_f32_e32 v17, v17, v6
	v_mul_f32_e32 v6, 0x3d372713, v18
	v_mul_f32_e32 v6, v18, v6
	v_fma_f32 v6, v18, v6, v18
	v_mul_f32_e32 v6, 0x3f4c422a, v6
	v_add_f32_e32 v6, v6, v6
	v_mul_f32_e32 v6, 0xbfb8aa3b, v6
	v_exp_f32_e32 v6, v6
	s_nop 0
	v_add_f32_e32 v6, 1.0, v6
	v_rcp_f32_e32 v6, v6
	s_nop 0
	v_mul_f32_e32 v9, v18, v6
	v_rcp_f32_e32 v18, v2
	v_mul_f32_e32 v2, 0xbfb8aa3b, v3
	v_exp_f32_e32 v2, v2
	v_and_b32_e32 v6, 0xffff0000, v140
	v_pk_mul_f32 v[14:15], v[18:19], v[14:15]
	v_add_f32_e32 v2, 1.0, v2
	v_rcp_f32_e32 v3, v2
	v_mul_f32_e32 v2, 0xbfb8aa3b, v6
	v_exp_f32_e32 v2, v2
	v_mul_f32_e32 v8, v14, v15
	v_add_f32_e32 v2, 1.0, v2
	v_rcp_f32_e32 v2, v2
	s_nop 0
	v_pk_mul_f32 v[2:3], v[2:3], v[6:7]
	s_nop 0
	v_mul_f32_e32 v2, v2, v3
	v_mul_f32_e32 v3, 0xbfb8aa3b, v4
	v_mul_f32_e32 v4, 0xbfb8aa3b, v5
	v_exp_f32_e32 v3, v3
	v_exp_f32_e32 v4, v4
	v_cvt_pk_bf16_f32 v2, v8, v2
	v_and_b32_e32 v8, 0xffff0000, v141
	v_add_f32_e32 v3, 1.0, v3
	v_add_f32_e32 v4, 1.0, v4
	v_rcp_f32_e32 v7, v3
	v_mul_f32_e32 v3, 0xbfb8aa3b, v16
	v_rcp_f32_e32 v5, v4
	v_mul_f32_e32 v4, 0xbfb8aa3b, v8
	v_exp_f32_e32 v3, v3
	v_exp_f32_e32 v4, v4
	v_add_f32_e32 v3, 1.0, v3
	v_add_f32_e32 v4, 1.0, v4
	v_rcp_f32_e32 v6, v3
	v_rcp_f32_e32 v4, v4
	v_pk_mul_f32 v[6:7], v[6:7], v[16:17]
	v_pk_mul_f32 v[4:5], v[4:5], v[8:9]
	v_mul_f32_e32 v3, v6, v7
	v_mul_f32_e32 v4, v4, v5
	v_cvt_pk_bf16_f32 v3, v3, v4
	v_lshl_add_u64 v[4:5], v[20:21], 0, v[138:139]
	global_store_dwordx2 v[4:5], v[2:3], off
	s_cbranch_scc0 .LBB0_1282
	s_branch .Lmy_shLBB01283
	s_nop 0
	s_nop 0
	s_nop 0
	s_nop 0
	s_nop 0
	s_nop 0
	s_nop 0
	s_nop 0
	s_nop 0
	s_nop 0
	s_nop 0
	s_nop 0

; #define EM_LOAD(st_, A_, B_) do { _Pragma("unroll") for (int bj_ = 0; bj_ < 2; ++bj_) { const unsigned char* mp_ = mbase + (size_t)(((st_) >> 2) * HALF + ((st_) & 3) * 16) * (INP * 2) + bj_ * HALF; A_[bj_] = *(const u32x2*)mp_; if (n < 3) B_[bj_] = *(const u32x2*)(mp_ + 1024); } } while (0)
;     __device__ __forceinline__ bool operator()(f32x4 (&acc)[2][2][4][2], const Unit& u, int wr, int wc, int fr, int fq) const {
;         const int row0 = u.pm * BM + wr * 64 + fr, col0 = u.pn * BM + wc * 32 + 8 * fq, n = u.z;
;         const unsigned char* mbase = (const unsigned char*)(P + (size_t)row0 * INP + OFF_MERGE) + n * 1024 + col0;
;         u32x2 ca[2], cb[2], na[2], nb[2];
;     ...
;         EM_LOAD(0, ca, cb);
; #pragma unroll
;         for (int st = 0; st < 8; ++st) { const int ai = st >> 2, m = st & 3;
;             if (st < 7) EM_LOAD(st + 1, na, nb);
.LBB0_1345:
	v_lshl_add_u32 v158, s40, 8, v176
	s_nop 0
	v_mov_b64_e32 v[2:3], s[42:43]
	v_lshl_or_b32 v148, s4, 8, v178
	v_mad_i64_i32 v[2:3], s[4:5], v158, s84, v[2:3]
	s_lshl_b32 s88, s1, 10
	v_lshl_add_u64 v[2:3], v[2:3], 0, s[88:89]
	v_ashrrev_i32_e32 v149, 31, v148
	v_lshl_add_u64 v[4:5], v[2:3], 0, v[148:149]
	v_add_co_u32_e32 v2, vcc, 0x8eb9000, v4
	s_mov_b64 s[4:5], 0x8eb9140
	s_nop 0
	v_addc_co_u32_e32 v3, vcc, 0, v5, vcc
	global_load_dwordx2 v[2:3], v[2:3], off offset:320
	s_cmp_eq_u32 s1, 3
	v_lshl_add_u64 v[156:157], v[4:5], 0, s[4:5]
	s_cselect_b64 s[4:5], -1, 0
	s_cmp_lg_u32 s1, 3
	s_cselect_b64 s[58:59], -1, 0
	v_mov_b32_e32 v160, 0
	s_and_b64 vcc, exec, s[4:5]
	v_mov_b32_e32 v168, 0
	v_mov_b32_e32 v169, 0
	s_cbranch_vccnz .LBB0_1347
	global_load_dwordx2 v[168:169], v[156:157], off offset:1024
.LBB0_1347:
	global_load_dwordx2 v[164:165], v[156:157], off offset:128
	v_cndmask_b32_e64 v4, 0, 1, s[58:59]
	v_cmp_ne_u32_e64 s[40:41], 1, v4
	s_andn2_b64 vcc, exec, s[58:59]
	v_mov_b32_e32 v161, 0
	s_movk_i32 s33, 0x2000
	s_cbranch_vccnz .LBB0_1349
	global_load_dwordx2 v[160:161], v[156:157], off offset:1152
.LBB0_1349:
	v_add_co_u32_e32 v4, vcc, 0x22000, v156
	s_nop 1
	v_addc_co_u32_e32 v5, vcc, 0, v157, vcc
	global_load_dwordx2 v[174:175], v[4:5], off
	s_and_b64 vcc, exec, s[40:41]
	s_cbranch_vccnz .LBB0_1351
	v_add_co_u32_e32 v4, vcc, 0x22000, v156
	s_nop 1
	v_addc_co_u32_e32 v5, vcc, 0, v157, vcc
	global_load_dwordx2 v[170:171], v[4:5], off offset:1024
.LBB0_1351:
	v_add_co_u32_e32 v4, vcc, 0x22000, v156
	s_nop 1
	v_addc_co_u32_e32 v5, vcc, 0, v157, vcc
	global_load_dwordx2 v[166:167], v[4:5], off offset:128
	s_and_b64 vcc, exec, s[40:41]
	s_cbranch_vccnz .LBB0_1353
	v_add_co_u32_e32 v4, vcc, 0x22000, v156
	s_nop 1
	v_addc_co_u32_e32 v5, vcc, 0, v157, vcc
	global_load_dwordx2 v[162:163], v[4:5], off offset:1152

; __device__ __forceinline__ unsigned cvt_pk_bf16(float lo, float hi) { unsigned r; asm volatile("v_cvt_pk_bf16_f32 %0, %1, %2" : "=v"(r) : "v"(lo), "v"(hi)); return r; }
;     __device__ __forceinline__ bool operator()(f32x4 (&acc)[2][2][4][2], const Unit& u, int wr, int wc, int fr, int fq) const {
;     ...
;                 f32x4 v0 = acc[ai][bj][m][0], v1 = acc[ai][bj][m][1];
;                 v0[0] *= f[0]; v0[1] *= f[1]; v0[2] *= f[2]; v0[3] *= f[3]; v1[0] *= f[4]; v1[1] *= f[5]; v1[2] *= f[6]; v1[3] *= f[7];
;                 acc[ai][bj][m][0] = v0; acc[ai][bj][m][1] = v1;
;                 if (n == 3) { u32x4 w; w.x = cvt_pk_bf16(v0[0], v0[1]); w.y = cvt_pk_bf16(v0[2], v0[3]); w.z = cvt_pk_bf16(v1[0], v1[1]); w.w = cvt_pk_bf16(v1[2], v1[3]);
;                     *(u32x4*)(Y + (size_t)(row0 + ai * HALF + m * 16) * 1024 + col0 + bj * HALF) = w; }
.LBB0_1357:
	v_ashrrev_i32_e32 v159, 31, v158
	v_lshlrev_b64 v[168:169], 11, v[158:159]
	v_pk_mul_f32 v[18:19], v[18:19], v[2:3]
	v_cndmask_b32_e64 v2, 0, 1, s[4:5]
	v_cmp_ne_u32_e64 s[38:39], 1, v2
	v_lshl_add_u64 v[2:3], s[46:47], 0, v[168:169]
	v_pk_mul_f32 v[20:21], v[20:21], v[4:5]
	v_pk_mul_f32 v[14:15], v[14:15], v[6:7]
	v_pk_mul_f32 v[16:17], v[16:17], v[8:9]
	s_andn2_b64 vcc, exec, s[4:5]
	v_lshl_add_u64 v[168:169], v[148:149], 1, v[2:3]
	s_cbranch_vccnz .LBB0_1359
	v_cvt_pk_bf16_f32 v2, v18, v19
	v_cvt_pk_bf16_f32 v3, v20, v21
	v_cvt_pk_bf16_f32 v4, v14, v15
	v_cvt_pk_bf16_f32 v5, v16, v17
	global_store_dwordx4 v[168:169], v[2:5], off

; __device__ __forceinline__ unsigned cvt_pk_bf16(float lo, float hi) { unsigned r; asm volatile("v_cvt_pk_bf16_f32 %0, %1, %2" : "=v"(r) : "v"(lo), "v"(hi)); return r; }
; #define EM_LOAD(st_, A_, B_) do { _Pragma("unroll") for (int bj_ = 0; bj_ < 2; ++bj_) { const unsigned char* mp_ = mbase + (size_t)(((st_) >> 2) * HALF + ((st_) & 3) * 16) * (INP * 2) + bj_ * HALF; A_[bj_] = *(const u32x2*)mp_; if (n < 3) B_[bj_] = *(const u32x2*)(mp_ + 1024); } } while (0)
;     __device__ __forceinline__ bool operator()(f32x4 (&acc)[2][2][4][2], const Unit& u, int wr, int wc, int fr, int fq) const {
;     ...
;         EM_LOAD(0, ca, cb);
; #pragma unroll
;         for (int st = 0; st < 8; ++st) { const int ai = st >> 2, m = st & 3;
;             if (st < 7) EM_LOAD(st + 1, na, nb);
;     ...
;                 f32x4 v0 = acc[ai][bj][m][0], v1 = acc[ai][bj][m][1];
;                 v0[0] *= f[0]; v0[1] *= f[1]; v0[2] *= f[2]; v0[3] *= f[3]; v1[0] *= f[4]; v1[1] *= f[5]; v1[2] *= f[6]; v1[3] *= f[7];
;                 acc[ai][bj][m][0] = v0; acc[ai][bj][m][1] = v1;
;                 if (n == 3) { u32x4 w; w.x = cvt_pk_bf16(v0[0], v0[1]); w.y = cvt_pk_bf16(v0[2], v0[3]); w.z = cvt_pk_bf16(v1[0], v1[1]); w.w = cvt_pk_bf16(v1[2], v1[3]);
;                     *(u32x4*)(Y + (size_t)(row0 + ai * HALF + m * 16) * 1024 + col0 + bj * HALF) = w; }
.LBB0_1363:
	v_pk_mul_f32 v[26:27], v[26:27], v[2:3]
	v_pk_mul_f32 v[28:29], v[28:29], v[4:5]
	v_pk_mul_f32 v[22:23], v[22:23], v[6:7]
	s_and_b64 vcc, exec, s[38:39]
	v_pk_mul_f32 v[24:25], v[24:25], v[8:9]
	s_cbranch_vccnz .LBB0_1365
	v_cvt_pk_bf16_f32 v2, v26, v27
	v_cvt_pk_bf16_f32 v3, v28, v29
	v_cvt_pk_bf16_f32 v4, v22, v23
	v_cvt_pk_bf16_f32 v5, v24, v25
	global_store_dwordx4 v[168:169], v[2:5], off offset:256
.LBB0_1365:
	s_nop 1
	v_add_co_u32_e32 v2, vcc, 0x44000, v156
	v_mov_b64_e32 v[168:169], v[170:171]
	s_nop 0
	v_addc_co_u32_e32 v3, vcc, 0, v157, vcc
	global_load_dwordx2 v[172:173], v[2:3], off
	s_and_b64 vcc, exec, s[40:41]
	s_cbranch_vccnz .LBB0_1367
	v_add_co_u32_e32 v2, vcc, 0x44000, v156
	s_nop 1
	v_addc_co_u32_e32 v3, vcc, 0, v157, vcc
	global_load_dwordx2 v[168:169], v[2:3], off offset:1024
.LBB0_1367:
	v_add_co_u32_e32 v2, vcc, 0x44000, v156
	v_mov_b64_e32 v[160:161], v[162:163]
	s_nop 0
	v_addc_co_u32_e32 v3, vcc, 0, v157, vcc
	global_load_dwordx2 v[164:165], v[2:3], off offset:128
	s_and_b64 vcc, exec, s[40:41]
	s_cbranch_vccnz .LBB0_1369
	v_add_co_u32_e32 v2, vcc, 0x44000, v156
	s_nop 1
	v_addc_co_u32_e32 v3, vcc, 0, v157, vcc
	global_load_dwordx2 v[160:161], v[2:3], off offset:1152

; __device__ __forceinline__ unsigned cvt_pk_bf16(float lo, float hi) { unsigned r; asm volatile("v_cvt_pk_bf16_f32 %0, %1, %2" : "=v"(r) : "v"(lo), "v"(hi)); return r; }
;     __device__ __forceinline__ bool operator()(f32x4 (&acc)[2][2][4][2], const Unit& u, int wr, int wc, int fr, int fq) const {
;     ...
;                 f32x4 v0 = acc[ai][bj][m][0], v1 = acc[ai][bj][m][1];
;                 v0[0] *= f[0]; v0[1] *= f[1]; v0[2] *= f[2]; v0[3] *= f[3]; v1[0] *= f[4]; v1[1] *= f[5]; v1[2] *= f[6]; v1[3] *= f[7];
;                 acc[ai][bj][m][0] = v0; acc[ai][bj][m][1] = v1;
;                 if (n == 3) { u32x4 w; w.x = cvt_pk_bf16(v0[0], v0[1]); w.y = cvt_pk_bf16(v0[2], v0[3]); w.z = cvt_pk_bf16(v1[0], v1[1]); w.w = cvt_pk_bf16(v1[2], v1[3]);
;                     *(u32x4*)(Y + (size_t)(row0 + ai * HALF + m * 16) * 1024 + col0 + bj * HALF) = w; }
.LBB0_1373:
	v_or_b32_e32 v170, 16, v158
	v_ashrrev_i32_e32 v171, 31, v170
	v_lshlrev_b64 v[170:171], 11, v[170:171]
	v_pk_mul_f32 v[34:35], v[34:35], v[2:3]
	v_lshl_add_u64 v[2:3], s[46:47], 0, v[170:171]
	v_pk_mul_f32 v[36:37], v[36:37], v[4:5]
	v_pk_mul_f32 v[30:31], v[30:31], v[6:7]
	v_pk_mul_f32 v[32:33], v[32:33], v[8:9]
	s_and_b64 vcc, exec, s[38:39]
	v_lshl_add_u64 v[170:171], v[148:149], 1, v[2:3]
	s_cbranch_vccnz .LBB0_1375
	v_cvt_pk_bf16_f32 v2, v34, v35
	v_cvt_pk_bf16_f32 v3, v36, v37
	v_cvt_pk_bf16_f32 v4, v30, v31
	v_cvt_pk_bf16_f32 v5, v32, v33
	global_store_dwordx4 v[170:171], v[2:5], off

; __device__ __forceinline__ unsigned cvt_pk_bf16(float lo, float hi) { unsigned r; asm volatile("v_cvt_pk_bf16_f32 %0, %1, %2" : "=v"(r) : "v"(lo), "v"(hi)); return r; }
; #define EM_LOAD(st_, A_, B_) do { _Pragma("unroll") for (int bj_ = 0; bj_ < 2; ++bj_) { const unsigned char* mp_ = mbase + (size_t)(((st_) >> 2) * HALF + ((st_) & 3) * 16) * (INP * 2) + bj_ * HALF; A_[bj_] = *(const u32x2*)mp_; if (n < 3) B_[bj_] = *(const u32x2*)(mp_ + 1024); } } while (0)
;     __device__ __forceinline__ bool operator()(f32x4 (&acc)[2][2][4][2], const Unit& u, int wr, int wc, int fr, int fq) const {
;     ...
;         EM_LOAD(0, ca, cb);
; #pragma unroll
;         for (int st = 0; st < 8; ++st) { const int ai = st >> 2, m = st & 3;
;             if (st < 7) EM_LOAD(st + 1, na, nb);
;     ...
;                 f32x4 v0 = acc[ai][bj][m][0], v1 = acc[ai][bj][m][1];
;                 v0[0] *= f[0]; v0[1] *= f[1]; v0[2] *= f[2]; v0[3] *= f[3]; v1[0] *= f[4]; v1[1] *= f[5]; v1[2] *= f[6]; v1[3] *= f[7];
;                 acc[ai][bj][m][0] = v0; acc[ai][bj][m][1] = v1;
;                 if (n == 3) { u32x4 w; w.x = cvt_pk_bf16(v0[0], v0[1]); w.y = cvt_pk_bf16(v0[2], v0[3]); w.z = cvt_pk_bf16(v1[0], v1[1]); w.w = cvt_pk_bf16(v1[2], v1[3]);
;                     *(u32x4*)(Y + (size_t)(row0 + ai * HALF + m * 16) * 1024 + col0 + bj * HALF) = w; }
.LBB0_1379:
	v_pk_mul_f32 v[42:43], v[42:43], v[2:3]
	v_pk_mul_f32 v[44:45], v[44:45], v[4:5]
	v_pk_mul_f32 v[38:39], v[38:39], v[6:7]
	s_and_b64 vcc, exec, s[38:39]
	v_pk_mul_f32 v[40:41], v[40:41], v[8:9]
	s_cbranch_vccnz .LBB0_1381
	v_cvt_pk_bf16_f32 v2, v42, v43
	v_cvt_pk_bf16_f32 v3, v44, v45
	v_cvt_pk_bf16_f32 v4, v38, v39
	v_cvt_pk_bf16_f32 v5, v40, v41
	global_store_dwordx4 v[170:171], v[2:5], off offset:256
.LBB0_1381:
	s_nop 1
	v_add_co_u32_e32 v2, vcc, 0x66000, v156
	s_waitcnt vmcnt(0) lgkmcnt(0)
	v_mov_b64_e32 v[170:171], v[168:169]
	v_addc_co_u32_e32 v3, vcc, 0, v157, vcc
	global_load_dwordx2 v[174:175], v[2:3], off
	s_and_b64 vcc, exec, s[40:41]
	s_cbranch_vccnz .LBB0_1383
	v_add_co_u32_e32 v2, vcc, 0x66000, v156
	s_nop 1
	v_addc_co_u32_e32 v3, vcc, 0, v157, vcc
	global_load_dwordx2 v[170:171], v[2:3], off offset:1024
.LBB0_1383:
	v_add_co_u32_e32 v2, vcc, 0x66000, v156
	v_mov_b64_e32 v[162:163], v[160:161]
	s_nop 0
	v_addc_co_u32_e32 v3, vcc, 0, v157, vcc
	global_load_dwordx2 v[166:167], v[2:3], off offset:128
	s_and_b64 vcc, exec, s[40:41]
	s_cbranch_vccnz .LBB0_1385
	v_add_co_u32_e32 v2, vcc, 0x66000, v156
	s_nop 1
	v_addc_co_u32_e32 v3, vcc, 0, v157, vcc
	global_load_dwordx2 v[162:163], v[2:3], off offset:1152

; __device__ __forceinline__ unsigned cvt_pk_bf16(float lo, float hi) { unsigned r; asm volatile("v_cvt_pk_bf16_f32 %0, %1, %2" : "=v"(r) : "v"(lo), "v"(hi)); return r; }
;     __device__ __forceinline__ bool operator()(f32x4 (&acc)[2][2][4][2], const Unit& u, int wr, int wc, int fr, int fq) const {
;     ...
;                 f32x4 v0 = acc[ai][bj][m][0], v1 = acc[ai][bj][m][1];
;                 v0[0] *= f[0]; v0[1] *= f[1]; v0[2] *= f[2]; v0[3] *= f[3]; v1[0] *= f[4]; v1[1] *= f[5]; v1[2] *= f[6]; v1[3] *= f[7];
;                 acc[ai][bj][m][0] = v0; acc[ai][bj][m][1] = v1;
;                 if (n == 3) { u32x4 w; w.x = cvt_pk_bf16(v0[0], v0[1]); w.y = cvt_pk_bf16(v0[2], v0[3]); w.z = cvt_pk_bf16(v1[0], v1[1]); w.w = cvt_pk_bf16(v1[2], v1[3]);
;                     *(u32x4*)(Y + (size_t)(row0 + ai * HALF + m * 16) * 1024 + col0 + bj * HALF) = w; }
.LBB0_1389:
	v_or_b32_e32 v168, 32, v158
	v_ashrrev_i32_e32 v169, 31, v168
	v_lshlrev_b64 v[168:169], 11, v[168:169]
	v_pk_mul_f32 v[58:59], v[58:59], v[2:3]
	v_lshl_add_u64 v[2:3], s[46:47], 0, v[168:169]
	v_pk_mul_f32 v[60:61], v[60:61], v[4:5]
	v_pk_mul_f32 v[54:55], v[54:55], v[6:7]
	v_pk_mul_f32 v[56:57], v[56:57], v[8:9]
	s_and_b64 vcc, exec, s[38:39]
	v_lshl_add_u64 v[168:169], v[148:149], 1, v[2:3]
	s_cbranch_vccnz .LBB0_1391
	v_cvt_pk_bf16_f32 v2, v58, v59
	v_cvt_pk_bf16_f32 v3, v60, v61
	v_cvt_pk_bf16_f32 v4, v54, v55
	v_cvt_pk_bf16_f32 v5, v56, v57
	global_store_dwordx4 v[168:169], v[2:5], off

; __device__ __forceinline__ unsigned cvt_pk_bf16(float lo, float hi) { unsigned r; asm volatile("v_cvt_pk_bf16_f32 %0, %1, %2" : "=v"(r) : "v"(lo), "v"(hi)); return r; }
; #define EM_LOAD(st_, A_, B_) do { _Pragma("unroll") for (int bj_ = 0; bj_ < 2; ++bj_) { const unsigned char* mp_ = mbase + (size_t)(((st_) >> 2) * HALF + ((st_) & 3) * 16) * (INP * 2) + bj_ * HALF; A_[bj_] = *(const u32x2*)mp_; if (n < 3) B_[bj_] = *(const u32x2*)(mp_ + 1024); } } while (0)
;     __device__ __forceinline__ bool operator()(f32x4 (&acc)[2][2][4][2], const Unit& u, int wr, int wc, int fr, int fq) const {
;     ...
;         EM_LOAD(0, ca, cb);
; #pragma unroll
;         for (int st = 0; st < 8; ++st) { const int ai = st >> 2, m = st & 3;
;             if (st < 7) EM_LOAD(st + 1, na, nb);
;     ...
;                 f32x4 v0 = acc[ai][bj][m][0], v1 = acc[ai][bj][m][1];
;                 v0[0] *= f[0]; v0[1] *= f[1]; v0[2] *= f[2]; v0[3] *= f[3]; v1[0] *= f[4]; v1[1] *= f[5]; v1[2] *= f[6]; v1[3] *= f[7];
;                 acc[ai][bj][m][0] = v0; acc[ai][bj][m][1] = v1;
;                 if (n == 3) { u32x4 w; w.x = cvt_pk_bf16(v0[0], v0[1]); w.y = cvt_pk_bf16(v0[2], v0[3]); w.z = cvt_pk_bf16(v1[0], v1[1]); w.w = cvt_pk_bf16(v1[2], v1[3]);
;                     *(u32x4*)(Y + (size_t)(row0 + ai * HALF + m * 16) * 1024 + col0 + bj * HALF) = w; }
.LBB0_1395:
	v_pk_mul_f32 v[74:75], v[74:75], v[2:3]
	v_pk_mul_f32 v[76:77], v[76:77], v[4:5]
	v_pk_mul_f32 v[70:71], v[70:71], v[6:7]
	s_and_b64 vcc, exec, s[38:39]
	v_pk_mul_f32 v[72:73], v[72:73], v[8:9]
	s_cbranch_vccnz .LBB0_1397
	v_cvt_pk_bf16_f32 v2, v74, v75
	v_cvt_pk_bf16_f32 v3, v76, v77
	v_cvt_pk_bf16_f32 v4, v70, v71
	v_cvt_pk_bf16_f32 v5, v72, v73
	global_store_dwordx4 v[168:169], v[2:5], off offset:256
.LBB0_1397:
	s_nop 1
	v_add_co_u32_e32 v2, vcc, 0x110000, v156
	s_waitcnt vmcnt(0) lgkmcnt(0)
	v_mov_b64_e32 v[168:169], v[170:171]
	v_addc_co_u32_e32 v3, vcc, 0, v157, vcc
	global_load_dwordx2 v[172:173], v[2:3], off
	s_and_b64 vcc, exec, s[40:41]
	s_cbranch_vccnz .LBB0_1399
	v_add_co_u32_e32 v2, vcc, 0x110000, v156
	s_nop 1
	v_addc_co_u32_e32 v3, vcc, 0, v157, vcc
	global_load_dwordx2 v[168:169], v[2:3], off offset:1024
.LBB0_1399:
	v_add_co_u32_e32 v2, vcc, 0x110000, v156
	v_mov_b64_e32 v[160:161], v[162:163]
	s_nop 0
	v_addc_co_u32_e32 v3, vcc, 0, v157, vcc
	global_load_dwordx2 v[164:165], v[2:3], off offset:128
	s_and_b64 vcc, exec, s[40:41]
	s_cbranch_vccnz .LBB0_1401
	v_add_co_u32_e32 v2, vcc, 0x110000, v156
	s_nop 1
	v_addc_co_u32_e32 v3, vcc, 0, v157, vcc
	global_load_dwordx2 v[160:161], v[2:3], off offset:1152

; __device__ __forceinline__ unsigned cvt_pk_bf16(float lo, float hi) { unsigned r; asm volatile("v_cvt_pk_bf16_f32 %0, %1, %2" : "=v"(r) : "v"(lo), "v"(hi)); return r; }
;     __device__ __forceinline__ bool operator()(f32x4 (&acc)[2][2][4][2], const Unit& u, int wr, int wc, int fr, int fq) const {
;     ...
;                 f32x4 v0 = acc[ai][bj][m][0], v1 = acc[ai][bj][m][1];
;                 v0[0] *= f[0]; v0[1] *= f[1]; v0[2] *= f[2]; v0[3] *= f[3]; v1[0] *= f[4]; v1[1] *= f[5]; v1[2] *= f[6]; v1[3] *= f[7];
;                 acc[ai][bj][m][0] = v0; acc[ai][bj][m][1] = v1;
;                 if (n == 3) { u32x4 w; w.x = cvt_pk_bf16(v0[0], v0[1]); w.y = cvt_pk_bf16(v0[2], v0[3]); w.z = cvt_pk_bf16(v1[0], v1[1]); w.w = cvt_pk_bf16(v1[2], v1[3]);
;                     *(u32x4*)(Y + (size_t)(row0 + ai * HALF + m * 16) * 1024 + col0 + bj * HALF) = w; }
.LBB0_1405:
	v_or_b32_e32 v170, 48, v158
	v_ashrrev_i32_e32 v171, 31, v170
	v_lshlrev_b64 v[170:171], 11, v[170:171]
	v_pk_mul_f32 v[90:91], v[90:91], v[2:3]
	v_lshl_add_u64 v[2:3], s[46:47], 0, v[170:171]
	v_pk_mul_f32 v[92:93], v[92:93], v[4:5]
	v_pk_mul_f32 v[86:87], v[86:87], v[6:7]
	v_pk_mul_f32 v[88:89], v[88:89], v[8:9]
	s_and_b64 vcc, exec, s[38:39]
	v_lshl_add_u64 v[170:171], v[148:149], 1, v[2:3]
	s_cbranch_vccnz .LBB0_1407
	v_cvt_pk_bf16_f32 v2, v90, v91
	v_cvt_pk_bf16_f32 v3, v92, v93
	v_cvt_pk_bf16_f32 v4, v86, v87
	v_cvt_pk_bf16_f32 v5, v88, v89
	global_store_dwordx4 v[170:171], v[2:5], off

; __device__ __forceinline__ unsigned cvt_pk_bf16(float lo, float hi) { unsigned r; asm volatile("v_cvt_pk_bf16_f32 %0, %1, %2" : "=v"(r) : "v"(lo), "v"(hi)); return r; }
; #define EM_LOAD(st_, A_, B_) do { _Pragma("unroll") for (int bj_ = 0; bj_ < 2; ++bj_) { const unsigned char* mp_ = mbase + (size_t)(((st_) >> 2) * HALF + ((st_) & 3) * 16) * (INP * 2) + bj_ * HALF; A_[bj_] = *(const u32x2*)mp_; if (n < 3) B_[bj_] = *(const u32x2*)(mp_ + 1024); } } while (0)
;     __device__ __forceinline__ bool operator()(f32x4 (&acc)[2][2][4][2], const Unit& u, int wr, int wc, int fr, int fq) const {
;     ...
;         EM_LOAD(0, ca, cb);
; #pragma unroll
;         for (int st = 0; st < 8; ++st) { const int ai = st >> 2, m = st & 3;
;             if (st < 7) EM_LOAD(st + 1, na, nb);
;     ...
;                 f32x4 v0 = acc[ai][bj][m][0], v1 = acc[ai][bj][m][1];
;                 v0[0] *= f[0]; v0[1] *= f[1]; v0[2] *= f[2]; v0[3] *= f[3]; v1[0] *= f[4]; v1[1] *= f[5]; v1[2] *= f[6]; v1[3] *= f[7];
;                 acc[ai][bj][m][0] = v0; acc[ai][bj][m][1] = v1;
;                 if (n == 3) { u32x4 w; w.x = cvt_pk_bf16(v0[0], v0[1]); w.y = cvt_pk_bf16(v0[2], v0[3]); w.z = cvt_pk_bf16(v1[0], v1[1]); w.w = cvt_pk_bf16(v1[2], v1[3]);
;                     *(u32x4*)(Y + (size_t)(row0 + ai * HALF + m * 16) * 1024 + col0 + bj * HALF) = w; }
.LBB0_1411:
	v_pk_mul_f32 v[106:107], v[106:107], v[2:3]
	v_pk_mul_f32 v[108:109], v[108:109], v[4:5]
	v_pk_mul_f32 v[102:103], v[102:103], v[6:7]
	s_and_b64 vcc, exec, s[38:39]
	v_pk_mul_f32 v[104:105], v[104:105], v[8:9]
	s_cbranch_vccnz .LBB0_1413
	v_cvt_pk_bf16_f32 v2, v106, v107
	v_cvt_pk_bf16_f32 v3, v108, v109
	v_cvt_pk_bf16_f32 v4, v102, v103
	v_cvt_pk_bf16_f32 v5, v104, v105
	global_store_dwordx4 v[170:171], v[2:5], off offset:256
.LBB0_1413:
	s_nop 1
	v_add_co_u32_e32 v2, vcc, 0x132000, v156
	s_waitcnt vmcnt(0) lgkmcnt(0)
	v_mov_b64_e32 v[170:171], v[168:169]
	v_addc_co_u32_e32 v3, vcc, 0, v157, vcc
	global_load_dwordx2 v[174:175], v[2:3], off
	s_and_b64 vcc, exec, s[40:41]
	s_cbranch_vccnz .LBB0_1415
	v_add_co_u32_e32 v2, vcc, 0x132000, v156
	s_nop 1
	v_addc_co_u32_e32 v3, vcc, 0, v157, vcc
	global_load_dwordx2 v[170:171], v[2:3], off offset:1024
.LBB0_1415:
	v_add_co_u32_e32 v2, vcc, 0x132000, v156
	v_mov_b64_e32 v[162:163], v[160:161]
	s_nop 0
	v_addc_co_u32_e32 v3, vcc, 0, v157, vcc
	global_load_dwordx2 v[166:167], v[2:3], off offset:128
	s_and_b64 vcc, exec, s[40:41]
	s_cbranch_vccnz .LBB0_1417
	v_add_co_u32_e32 v2, vcc, 0x132000, v156
	s_nop 1
	v_addc_co_u32_e32 v3, vcc, 0, v157, vcc
	global_load_dwordx2 v[162:163], v[2:3], off offset:1152

; __device__ __forceinline__ unsigned cvt_pk_bf16(float lo, float hi) { unsigned r; asm volatile("v_cvt_pk_bf16_f32 %0, %1, %2" : "=v"(r) : "v"(lo), "v"(hi)); return r; }
;     __device__ __forceinline__ bool operator()(f32x4 (&acc)[2][2][4][2], const Unit& u, int wr, int wc, int fr, int fq) const {
;     ...
;                 f32x4 v0 = acc[ai][bj][m][0], v1 = acc[ai][bj][m][1];
;                 v0[0] *= f[0]; v0[1] *= f[1]; v0[2] *= f[2]; v0[3] *= f[3]; v1[0] *= f[4]; v1[1] *= f[5]; v1[2] *= f[6]; v1[3] *= f[7];
;                 acc[ai][bj][m][0] = v0; acc[ai][bj][m][1] = v1;
;                 if (n == 3) { u32x4 w; w.x = cvt_pk_bf16(v0[0], v0[1]); w.y = cvt_pk_bf16(v0[2], v0[3]); w.z = cvt_pk_bf16(v1[0], v1[1]); w.w = cvt_pk_bf16(v1[2], v1[3]);
;                     *(u32x4*)(Y + (size_t)(row0 + ai * HALF + m * 16) * 1024 + col0 + bj * HALF) = w; }
.LBB0_1421:
	v_add_u32_e32 v158, 0x80, v158
	v_ashrrev_i32_e32 v159, 31, v158
	v_lshlrev_b64 v[168:169], 11, v[158:159]
	v_pk_mul_f32 v[122:123], v[122:123], v[2:3]
	v_lshl_add_u64 v[2:3], s[46:47], 0, v[168:169]
	v_pk_mul_f32 v[124:125], v[124:125], v[4:5]
	v_pk_mul_f32 v[118:119], v[118:119], v[6:7]
	v_pk_mul_f32 v[120:121], v[120:121], v[8:9]
	s_and_b64 vcc, exec, s[38:39]
	v_lshl_add_u64 v[168:169], v[148:149], 1, v[2:3]
	s_cbranch_vccnz .LBB0_1423
	v_cvt_pk_bf16_f32 v2, v122, v123
	v_cvt_pk_bf16_f32 v3, v124, v125
	v_cvt_pk_bf16_f32 v4, v118, v119
	v_cvt_pk_bf16_f32 v5, v120, v121
	global_store_dwordx4 v[168:169], v[2:5], off

; __device__ __forceinline__ unsigned cvt_pk_bf16(float lo, float hi) { unsigned r; asm volatile("v_cvt_pk_bf16_f32 %0, %1, %2" : "=v"(r) : "v"(lo), "v"(hi)); return r; }
; #define EM_LOAD(st_, A_, B_) do { _Pragma("unroll") for (int bj_ = 0; bj_ < 2; ++bj_) { const unsigned char* mp_ = mbase + (size_t)(((st_) >> 2) * HALF + ((st_) & 3) * 16) * (INP * 2) + bj_ * HALF; A_[bj_] = *(const u32x2*)mp_; if (n < 3) B_[bj_] = *(const u32x2*)(mp_ + 1024); } } while (0)
;     __device__ __forceinline__ bool operator()(f32x4 (&acc)[2][2][4][2], const Unit& u, int wr, int wc, int fr, int fq) const {
;     ...
;         EM_LOAD(0, ca, cb);
; #pragma unroll
;         for (int st = 0; st < 8; ++st) { const int ai = st >> 2, m = st & 3;
;             if (st < 7) EM_LOAD(st + 1, na, nb);
;     ...
;                 f32x4 v0 = acc[ai][bj][m][0], v1 = acc[ai][bj][m][1];
;                 v0[0] *= f[0]; v0[1] *= f[1]; v0[2] *= f[2]; v0[3] *= f[3]; v1[0] *= f[4]; v1[1] *= f[5]; v1[2] *= f[6]; v1[3] *= f[7];
;                 acc[ai][bj][m][0] = v0; acc[ai][bj][m][1] = v1;
;                 if (n == 3) { u32x4 w; w.x = cvt_pk_bf16(v0[0], v0[1]); w.y = cvt_pk_bf16(v0[2], v0[3]); w.z = cvt_pk_bf16(v1[0], v1[1]); w.w = cvt_pk_bf16(v1[2], v1[3]);
;                     *(u32x4*)(Y + (size_t)(row0 + ai * HALF + m * 16) * 1024 + col0 + bj * HALF) = w; }
.LBB0_1427:
	v_pk_mul_f32 v[130:131], v[130:131], v[2:3]
	v_pk_mul_f32 v[132:133], v[132:133], v[4:5]
	v_pk_mul_f32 v[126:127], v[126:127], v[6:7]
	s_and_b64 vcc, exec, s[38:39]
	v_pk_mul_f32 v[128:129], v[128:129], v[8:9]
	s_cbranch_vccnz .LBB0_1429
	v_cvt_pk_bf16_f32 v2, v130, v131
	v_cvt_pk_bf16_f32 v3, v132, v133
	v_cvt_pk_bf16_f32 v4, v126, v127
	v_cvt_pk_bf16_f32 v5, v128, v129
	global_store_dwordx4 v[168:169], v[2:5], off offset:256
.LBB0_1429:
	s_nop 1
	v_add_co_u32_e32 v2, vcc, 0x154000, v156
	s_waitcnt vmcnt(0) lgkmcnt(0)
	v_mov_b64_e32 v[168:169], v[170:171]
	v_addc_co_u32_e32 v3, vcc, 0, v157, vcc
	global_load_dwordx2 v[172:173], v[2:3], off
	s_and_b64 vcc, exec, s[40:41]
	s_cbranch_vccnz .LBB0_1431
	v_add_co_u32_e32 v2, vcc, 0x154000, v156
	s_nop 1
	v_addc_co_u32_e32 v3, vcc, 0, v157, vcc
	global_load_dwordx2 v[168:169], v[2:3], off offset:1024
.LBB0_1431:
	v_add_co_u32_e32 v2, vcc, 0x154000, v156
	v_mov_b64_e32 v[160:161], v[162:163]
	s_nop 0
	v_addc_co_u32_e32 v3, vcc, 0, v157, vcc
	global_load_dwordx2 v[164:165], v[2:3], off offset:128
	s_and_b64 vcc, exec, s[40:41]
	s_cbranch_vccnz .LBB0_1433
	v_add_co_u32_e32 v2, vcc, 0x154000, v156
	s_nop 1
	v_addc_co_u32_e32 v3, vcc, 0, v157, vcc
	global_load_dwordx2 v[160:161], v[2:3], off offset:1152

; __device__ __forceinline__ unsigned cvt_pk_bf16(float lo, float hi) { unsigned r; asm volatile("v_cvt_pk_bf16_f32 %0, %1, %2" : "=v"(r) : "v"(lo), "v"(hi)); return r; }
;     __device__ __forceinline__ bool operator()(f32x4 (&acc)[2][2][4][2], const Unit& u, int wr, int wc, int fr, int fq) const {
;     ...
;                 f32x4 v0 = acc[ai][bj][m][0], v1 = acc[ai][bj][m][1];
;                 v0[0] *= f[0]; v0[1] *= f[1]; v0[2] *= f[2]; v0[3] *= f[3]; v1[0] *= f[4]; v1[1] *= f[5]; v1[2] *= f[6]; v1[3] *= f[7];
;                 acc[ai][bj][m][0] = v0; acc[ai][bj][m][1] = v1;
;                 if (n == 3) { u32x4 w; w.x = cvt_pk_bf16(v0[0], v0[1]); w.y = cvt_pk_bf16(v0[2], v0[3]); w.z = cvt_pk_bf16(v1[0], v1[1]); w.w = cvt_pk_bf16(v1[2], v1[3]);
;                     *(u32x4*)(Y + (size_t)(row0 + ai * HALF + m * 16) * 1024 + col0 + bj * HALF) = w; }
.LBB0_1437:
	v_or_b32_e32 v170, 16, v158
	v_ashrrev_i32_e32 v171, 31, v170
	v_lshlrev_b64 v[170:171], 11, v[170:171]
	v_pk_mul_f32 v[138:139], v[138:139], v[2:3]
	v_lshl_add_u64 v[2:3], s[46:47], 0, v[170:171]
	v_pk_mul_f32 v[140:141], v[140:141], v[4:5]
	v_pk_mul_f32 v[134:135], v[134:135], v[6:7]
	v_pk_mul_f32 v[136:137], v[136:137], v[8:9]
	s_and_b64 vcc, exec, s[38:39]
	v_lshl_add_u64 v[170:171], v[148:149], 1, v[2:3]
	s_cbranch_vccnz .LBB0_1439
	v_cvt_pk_bf16_f32 v2, v138, v139
	v_cvt_pk_bf16_f32 v3, v140, v141
	v_cvt_pk_bf16_f32 v4, v134, v135
	v_cvt_pk_bf16_f32 v5, v136, v137
	global_store_dwordx4 v[170:171], v[2:5], off

; __device__ __forceinline__ unsigned cvt_pk_bf16(float lo, float hi) { unsigned r; asm volatile("v_cvt_pk_bf16_f32 %0, %1, %2" : "=v"(r) : "v"(lo), "v"(hi)); return r; }
; #define EM_LOAD(st_, A_, B_) do { _Pragma("unroll") for (int bj_ = 0; bj_ < 2; ++bj_) { const unsigned char* mp_ = mbase + (size_t)(((st_) >> 2) * HALF + ((st_) & 3) * 16) * (INP * 2) + bj_ * HALF; A_[bj_] = *(const u32x2*)mp_; if (n < 3) B_[bj_] = *(const u32x2*)(mp_ + 1024); } } while (0)
;     __device__ __forceinline__ bool operator()(f32x4 (&acc)[2][2][4][2], const Unit& u, int wr, int wc, int fr, int fq) const {
;     ...
;         EM_LOAD(0, ca, cb);
; #pragma unroll
;         for (int st = 0; st < 8; ++st) { const int ai = st >> 2, m = st & 3;
;             if (st < 7) EM_LOAD(st + 1, na, nb);
;     ...
;                 f32x4 v0 = acc[ai][bj][m][0], v1 = acc[ai][bj][m][1];
;                 v0[0] *= f[0]; v0[1] *= f[1]; v0[2] *= f[2]; v0[3] *= f[3]; v1[0] *= f[4]; v1[1] *= f[5]; v1[2] *= f[6]; v1[3] *= f[7];
;                 acc[ai][bj][m][0] = v0; acc[ai][bj][m][1] = v1;
;                 if (n == 3) { u32x4 w; w.x = cvt_pk_bf16(v0[0], v0[1]); w.y = cvt_pk_bf16(v0[2], v0[3]); w.z = cvt_pk_bf16(v1[0], v1[1]); w.w = cvt_pk_bf16(v1[2], v1[3]);
;                     *(u32x4*)(Y + (size_t)(row0 + ai * HALF + m * 16) * 1024 + col0 + bj * HALF) = w; }
.LBB0_1443:
	v_pk_mul_f32 v[114:115], v[114:115], v[2:3]
	v_pk_mul_f32 v[116:117], v[116:117], v[4:5]
	v_pk_mul_f32 v[110:111], v[110:111], v[6:7]
	s_and_b64 vcc, exec, s[38:39]
	v_pk_mul_f32 v[112:113], v[112:113], v[8:9]
	s_cbranch_vccnz .LBB0_1445
	v_cvt_pk_bf16_f32 v2, v114, v115
	v_cvt_pk_bf16_f32 v3, v116, v117
	v_cvt_pk_bf16_f32 v4, v110, v111
	v_cvt_pk_bf16_f32 v5, v112, v113
	global_store_dwordx4 v[170:171], v[2:5], off offset:256
.LBB0_1445:
	s_nop 1
	v_add_co_u32_e32 v2, vcc, 0x176000, v156
	s_waitcnt vmcnt(0) lgkmcnt(0)
	v_mov_b64_e32 v[170:171], v[168:169]
	v_addc_co_u32_e32 v3, vcc, 0, v157, vcc
	global_load_dwordx2 v[174:175], v[2:3], off
	s_and_b64 vcc, exec, s[40:41]
	s_cbranch_vccnz .LBB0_1447
	v_add_co_u32_e32 v2, vcc, 0x176000, v156
	s_nop 1
	v_addc_co_u32_e32 v3, vcc, 0, v157, vcc
	global_load_dwordx2 v[170:171], v[2:3], off offset:1024
.LBB0_1447:
	v_add_co_u32_e32 v2, vcc, 0x176000, v156
	v_mov_b64_e32 v[162:163], v[160:161]
	s_nop 0
	v_addc_co_u32_e32 v3, vcc, 0, v157, vcc
	global_load_dwordx2 v[166:167], v[2:3], off offset:128
	s_and_b64 vcc, exec, s[40:41]
	s_cbranch_vccnz .LBB0_1449
	v_add_co_u32_e32 v2, vcc, 0x176000, v156
	s_nop 1
	v_addc_co_u32_e32 v3, vcc, 0, v157, vcc
	global_load_dwordx2 v[162:163], v[2:3], off offset:1152

; __device__ __forceinline__ unsigned cvt_pk_bf16(float lo, float hi) { unsigned r; asm volatile("v_cvt_pk_bf16_f32 %0, %1, %2" : "=v"(r) : "v"(lo), "v"(hi)); return r; }
;     __device__ __forceinline__ bool operator()(f32x4 (&acc)[2][2][4][2], const Unit& u, int wr, int wc, int fr, int fq) const {
;     ...
;                 f32x4 v0 = acc[ai][bj][m][0], v1 = acc[ai][bj][m][1];
;                 v0[0] *= f[0]; v0[1] *= f[1]; v0[2] *= f[2]; v0[3] *= f[3]; v1[0] *= f[4]; v1[1] *= f[5]; v1[2] *= f[6]; v1[3] *= f[7];
;                 acc[ai][bj][m][0] = v0; acc[ai][bj][m][1] = v1;
;                 if (n == 3) { u32x4 w; w.x = cvt_pk_bf16(v0[0], v0[1]); w.y = cvt_pk_bf16(v0[2], v0[3]); w.z = cvt_pk_bf16(v1[0], v1[1]); w.w = cvt_pk_bf16(v1[2], v1[3]);
;                     *(u32x4*)(Y + (size_t)(row0 + ai * HALF + m * 16) * 1024 + col0 + bj * HALF) = w; }
.LBB0_1453:
	v_or_b32_e32 v156, 32, v158
	v_ashrrev_i32_e32 v157, 31, v156
	v_lshlrev_b64 v[156:157], 11, v[156:157]
	v_pk_mul_f32 v[98:99], v[98:99], v[2:3]
	v_lshl_add_u64 v[2:3], s[46:47], 0, v[156:157]
	v_pk_mul_f32 v[100:101], v[100:101], v[4:5]
	v_pk_mul_f32 v[94:95], v[94:95], v[6:7]
	v_pk_mul_f32 v[96:97], v[96:97], v[8:9]
	s_and_b64 vcc, exec, s[38:39]
	v_lshl_add_u64 v[156:157], v[148:149], 1, v[2:3]
	s_cbranch_vccnz .LBB0_1455
	v_cvt_pk_bf16_f32 v2, v98, v99
	v_cvt_pk_bf16_f32 v3, v100, v101
	v_cvt_pk_bf16_f32 v4, v94, v95
	v_cvt_pk_bf16_f32 v5, v96, v97
	global_store_dwordx4 v[156:157], v[2:5], off

; __device__ __forceinline__ unsigned cvt_pk_bf16(float lo, float hi) { unsigned r; asm volatile("v_cvt_pk_bf16_f32 %0, %1, %2" : "=v"(r) : "v"(lo), "v"(hi)); return r; }
;     __device__ __forceinline__ bool operator()(f32x4 (&acc)[2][2][4][2], const Unit& u, int wr, int wc, int fr, int fq) const {
;     ...
;                 f32x4 v0 = acc[ai][bj][m][0], v1 = acc[ai][bj][m][1];
;                 v0[0] *= f[0]; v0[1] *= f[1]; v0[2] *= f[2]; v0[3] *= f[3]; v1[0] *= f[4]; v1[1] *= f[5]; v1[2] *= f[6]; v1[3] *= f[7];
;                 acc[ai][bj][m][0] = v0; acc[ai][bj][m][1] = v1;
;                 if (n == 3) { u32x4 w; w.x = cvt_pk_bf16(v0[0], v0[1]); w.y = cvt_pk_bf16(v0[2], v0[3]); w.z = cvt_pk_bf16(v1[0], v1[1]); w.w = cvt_pk_bf16(v1[2], v1[3]);
;                     *(u32x4*)(Y + (size_t)(row0 + ai * HALF + m * 16) * 1024 + col0 + bj * HALF) = w; }
.LBB0_1459:
	v_pk_mul_f32 v[82:83], v[82:83], v[2:3]
	v_pk_mul_f32 v[84:85], v[84:85], v[4:5]
	v_pk_mul_f32 v[78:79], v[78:79], v[6:7]
	s_and_b64 vcc, exec, s[38:39]
	v_pk_mul_f32 v[80:81], v[80:81], v[8:9]
	s_cbranch_vccnz .LBB0_1461
	v_cvt_pk_bf16_f32 v2, v82, v83
	v_cvt_pk_bf16_f32 v3, v84, v85
	v_cvt_pk_bf16_f32 v4, v78, v79
	v_cvt_pk_bf16_f32 v5, v80, v81
	global_store_dwordx4 v[156:157], v[2:5], off offset:256

; __device__ __forceinline__ unsigned cvt_pk_bf16(float lo, float hi) { unsigned r; asm volatile("v_cvt_pk_bf16_f32 %0, %1, %2" : "=v"(r) : "v"(lo), "v"(hi)); return r; }
;     __device__ __forceinline__ bool operator()(f32x4 (&acc)[2][2][4][2], const Unit& u, int wr, int wc, int fr, int fq) const {
;     ...
;                 f32x4 v0 = acc[ai][bj][m][0], v1 = acc[ai][bj][m][1];
;                 v0[0] *= f[0]; v0[1] *= f[1]; v0[2] *= f[2]; v0[3] *= f[3]; v1[0] *= f[4]; v1[1] *= f[5]; v1[2] *= f[6]; v1[3] *= f[7];
;                 acc[ai][bj][m][0] = v0; acc[ai][bj][m][1] = v1;
;                 if (n == 3) { u32x4 w; w.x = cvt_pk_bf16(v0[0], v0[1]); w.y = cvt_pk_bf16(v0[2], v0[3]); w.z = cvt_pk_bf16(v1[0], v1[1]); w.w = cvt_pk_bf16(v1[2], v1[3]);
;                     *(u32x4*)(Y + (size_t)(row0 + ai * HALF + m * 16) * 1024 + col0 + bj * HALF) = w; }
.LBB0_1465:
	v_or_b32_e32 v156, 48, v158
	v_ashrrev_i32_e32 v157, 31, v156
	v_lshlrev_b64 v[156:157], 11, v[156:157]
	v_pk_mul_f32 v[66:67], v[66:67], v[2:3]
	v_lshl_add_u64 v[2:3], s[46:47], 0, v[156:157]
	v_pk_mul_f32 v[68:69], v[68:69], v[4:5]
	v_pk_mul_f32 v[62:63], v[62:63], v[6:7]
	v_pk_mul_f32 v[64:65], v[64:65], v[8:9]
	s_and_b64 vcc, exec, s[38:39]
	v_lshl_add_u64 v[148:149], v[148:149], 1, v[2:3]
	s_cbranch_vccnz .LBB0_1467
	v_cvt_pk_bf16_f32 v2, v66, v67
	v_cvt_pk_bf16_f32 v3, v68, v69
	v_cvt_pk_bf16_f32 v4, v62, v63
	v_cvt_pk_bf16_f32 v5, v64, v65
	global_store_dwordx4 v[148:149], v[2:5], off

; __device__ __forceinline__ unsigned cvt_pk_bf16(float lo, float hi) { unsigned r; asm volatile("v_cvt_pk_bf16_f32 %0, %1, %2" : "=v"(r) : "v"(lo), "v"(hi)); return r; }
;     __device__ __forceinline__ bool operator()(f32x4 (&acc)[2][2][4][2], const Unit& u, int wr, int wc, int fr, int fq) const {
;     ...
;                 f32x4 v0 = acc[ai][bj][m][0], v1 = acc[ai][bj][m][1];
;                 v0[0] *= f[0]; v0[1] *= f[1]; v0[2] *= f[2]; v0[3] *= f[3]; v1[0] *= f[4]; v1[1] *= f[5]; v1[2] *= f[6]; v1[3] *= f[7];
;                 acc[ai][bj][m][0] = v0; acc[ai][bj][m][1] = v1;
;                 if (n == 3) { u32x4 w; w.x = cvt_pk_bf16(v0[0], v0[1]); w.y = cvt_pk_bf16(v0[2], v0[3]); w.z = cvt_pk_bf16(v1[0], v1[1]); w.w = cvt_pk_bf16(v1[2], v1[3]);
;                     *(u32x4*)(Y + (size_t)(row0 + ai * HALF + m * 16) * 1024 + col0 + bj * HALF) = w; }
.LBB0_1471:
	v_pk_mul_f32 v[50:51], v[50:51], v[2:3]
	v_pk_mul_f32 v[52:53], v[52:53], v[4:5]
	v_pk_mul_f32 v[2:3], v[46:47], v[6:7]
	s_and_b64 vcc, exec, s[38:39]
	v_pk_mul_f32 v[4:5], v[48:49], v[8:9]
	s_cbranch_vccnz .LBB0_1473
	v_cvt_pk_bf16_f32 v6, v50, v51
	v_cvt_pk_bf16_f32 v7, v52, v53
	v_cvt_pk_bf16_f32 v8, v2, v3
	v_cvt_pk_bf16_f32 v9, v4, v5
	global_store_dwordx4 v[148:149], v[6:9], off offset:256

; #define LAS __attribute__((address_space(3)))
; __device__ __forceinline__ void p0_transpose_item(const float* W, int K, int N, bf16_t* WT, LAS float* scr, int item, int lane) {
;     const int nblk = N / 32, kb = item / nblk, nb = item % nblk, k0 = 64 * kb, n0 = 32 * nb;
;     float tv[32];
; #pragma unroll
;     for (int i = 0; i < 32; ++i) tv[i] = W[(size_t)(k0 + 2 * i + (lane >> 5)) * N + n0 + (lane & 31)];
.LBB0_1484:
	s_mul_hi_i32 s4, s18, 0x532ae21d
	s_lshr_b32 s5, s4, 31
	s_ashr_i32 s4, s4, 6
	s_add_i32 s4, s4, s5
	s_lshl_b32 s36, s4, 6
	s_mulk_i32 s4, 0xe760
	s_add_i32 s4, s6, s4
	s_ashr_i32 s5, s4, 31
	v_or_b32_e32 v40, s36, v32
	v_lshl_add_u64 v[2:3], s[4:5], 2, v[16:17]
	v_mad_i64_i32 v[4:5], s[14:15], v40, s19, v[2:3]
	global_load_dword v4, v[4:5], off
	v_or_b32_e32 v5, 2, v40
	v_mad_i64_i32 v[20:21], s[14:15], v5, s19, v[2:3]
	global_load_dword v5, v[20:21], off
	v_or_b32_e32 v20, 4, v40
	v_mad_i64_i32 v[20:21], s[14:15], v20, s19, v[2:3]
	global_load_dword v20, v[20:21], off
	v_or_b32_e32 v21, 6, v40
	v_mad_i64_i32 v[22:23], s[14:15], v21, s19, v[2:3]
	global_load_dword v21, v[22:23], off
	v_or_b32_e32 v22, 8, v40
	v_mad_i64_i32 v[22:23], s[14:15], v22, s19, v[2:3]
	global_load_dword v22, v[22:23], off
	v_or_b32_e32 v23, 10, v40
	v_mad_i64_i32 v[34:35], s[14:15], v23, s19, v[2:3]
	v_or_b32_e32 v31, 12, v40
	global_load_dword v23, v[34:35], off
	v_mad_i64_i32 v[34:35], s[14:15], v31, s19, v[2:3]
	v_or_b32_e32 v33, 14, v40
	global_load_dword v31, v[34:35], off
	v_mad_i64_i32 v[34:35], s[14:15], v33, s19, v[2:3]
	global_load_dword v33, v[34:35], off
	v_or_b32_e32 v34, 16, v40
	v_mad_i64_i32 v[34:35], s[14:15], v34, s19, v[2:3]
	global_load_dword v34, v[34:35], off
	v_or_b32_e32 v35, 18, v40
	v_mad_i64_i32 v[36:37], s[14:15], v35, s19, v[2:3]
	global_load_dword v35, v[36:37], off
	v_or_b32_e32 v36, 20, v40
	v_mad_i64_i32 v[36:37], s[14:15], v36, s19, v[2:3]
	global_load_dword v36, v[36:37], off
	v_or_b32_e32 v37, 22, v40
	v_mad_i64_i32 v[38:39], s[14:15], v37, s19, v[2:3]
	global_load_dword v37, v[38:39], off
	v_or_b32_e32 v38, 24, v40
	v_mad_i64_i32 v[38:39], s[14:15], v38, s19, v[2:3]
	global_load_dword v41, v[38:39], off
	v_or_b32_e32 v38, 26, v40
	v_mad_i64_i32 v[38:39], s[14:15], v38, s19, v[2:3]
	global_load_dword v42, v[38:39], off
	v_or_b32_e32 v38, 28, v40
	v_mad_i64_i32 v[38:39], s[14:15], v38, s19, v[2:3]
	global_load_dword v43, v[38:39], off
	v_or_b32_e32 v38, 30, v40
	v_mad_i64_i32 v[38:39], s[14:15], v38, s19, v[2:3]
	global_load_dword v44, v[38:39], off
	v_or_b32_e32 v38, 32, v40
	v_mad_i64_i32 v[38:39], s[14:15], v38, s19, v[2:3]
	global_load_dword v45, v[38:39], off
	v_or_b32_e32 v38, 34, v40
	v_mad_i64_i32 v[38:39], s[14:15], v38, s19, v[2:3]
	global_load_dword v46, v[38:39], off
	v_or_b32_e32 v38, 36, v40
	v_mad_i64_i32 v[38:39], s[14:15], v38, s19, v[2:3]
	global_load_dword v47, v[38:39], off
	v_or_b32_e32 v38, 38, v40
	v_mad_i64_i32 v[38:39], s[14:15], v38, s19, v[2:3]
	global_load_dword v48, v[38:39], off
	v_or_b32_e32 v38, 40, v40
	v_mad_i64_i32 v[38:39], s[14:15], v38, s19, v[2:3]
	global_load_dword v49, v[38:39], off
	v_or_b32_e32 v38, 42, v40
	v_mad_i64_i32 v[38:39], s[14:15], v38, s19, v[2:3]
	global_load_dword v50, v[38:39], off
	v_or_b32_e32 v38, 44, v40
	v_mad_i64_i32 v[38:39], s[14:15], v38, s19, v[2:3]
	global_load_dword v51, v[38:39], off
	v_or_b32_e32 v38, 46, v40
	v_mad_i64_i32 v[38:39], s[14:15], v38, s19, v[2:3]
	global_load_dword v52, v[38:39], off
	v_or_b32_e32 v38, 48, v40
	v_mad_i64_i32 v[38:39], s[14:15], v38, s19, v[2:3]
	global_load_dword v53, v[38:39], off
	v_or_b32_e32 v38, 50, v40
	v_mad_i64_i32 v[38:39], s[14:15], v38, s19, v[2:3]
	global_load_dword v54, v[38:39], off
	v_or_b32_e32 v38, 52, v40
	v_mad_i64_i32 v[38:39], s[14:15], v38, s19, v[2:3]
	global_load_dword v55, v[38:39], off
	v_or_b32_e32 v38, 54, v40
	v_mad_i64_i32 v[38:39], s[14:15], v38, s19, v[2:3]
	global_load_dword v56, v[38:39], off
	v_or_b32_e32 v38, 56, v40
	v_mad_i64_i32 v[38:39], s[14:15], v38, s19, v[2:3]
	global_load_dword v57, v[38:39], off
	v_or_b32_e32 v38, 58, v40
	v_mad_i64_i32 v[38:39], s[14:15], v38, s19, v[2:3]
	global_load_dword v58, v[38:39], off
	v_or_b32_e32 v38, 60, v40
	v_mad_i64_i32 v[38:39], s[14:15], v38, s19, v[2:3]
	global_load_dword v38, v[38:39], off
	v_or_b32_e32 v39, 62, v40
	v_mad_i64_i32 v[2:3], s[14:15], v39, s19, v[2:3]
	global_load_dword v2, v[2:3], off
	v_add_u32_e32 v3, 0x400, v30
	s_waitcnt vmcnt(0)
; #define LAS __attribute__((address_space(3)))
; __device__ __forceinline__ unsigned cvt_pk_bf16(float lo, float hi) { unsigned r; asm volatile("v_cvt_pk_bf16_f32 %0, %1, %2" : "=v"(r) : "v"(lo), "v"(hi)); return r; }
; __device__ __forceinline__ void p0_transpose_item(const float* W, int K, int N, bf16_t* WT, LAS float* scr, int item, int lane) {
;     ...
; #pragma unroll
;     for (int i = 0; i < 32; ++i) scr[(2 * i + (lane >> 5)) * 33 + (lane & 31)] = tv[i];
;     asm volatile("s_waitcnt lgkmcnt(0)" ::: "memory");
;     const int c = lane & 7;
; #pragma unroll
;     for (int j = 0; j < 4; ++j) { const int n = (lane >> 3) + 8 * j; const LAS float* s = scr + (8 * c) * 33 + n;
;         u32x4 o; o.x = cvt_pk_bf16(s[0 * 33], s[1 * 33]); o.y = cvt_pk_bf16(s[2 * 33], s[3 * 33]); o.z = cvt_pk_bf16(s[4 * 33], s[5 * 33]); o.w = cvt_pk_bf16(s[6 * 33], s[7 * 33]);
;         *(u32x4*)(WT + (size_t)(n0 + n) * K + k0 + 8 * c) = o; }
;     asm volatile("s_waitcnt lgkmcnt(0)" ::: "memory");
	ds_write2_b32 v30, v4, v5 offset1:66
	ds_write2_b32 v30, v20, v21 offset0:132 offset1:198
	ds_write2_b32 v3, v22, v23 offset0:8 offset1:74
	ds_write2_b32 v3, v31, v33 offset0:140 offset1:206
	v_add_u32_e32 v3, 0x800, v30
	ds_write2_b32 v3, v34, v35 offset0:16 offset1:82
	ds_write2_b32 v3, v36, v37 offset0:148 offset1:214
	v_add_u32_e32 v3, 0xc00, v30
	ds_write2_b32 v3, v41, v42 offset0:24 offset1:90
	ds_write2_b32 v3, v43, v44 offset0:156 offset1:222
	v_add_u32_e32 v3, 0x1000, v30
	ds_write2_b32 v3, v45, v46 offset0:32 offset1:98
	ds_write2_b32 v3, v47, v48 offset0:164 offset1:230
	v_add_u32_e32 v3, 0x1400, v30
	ds_write2_b32 v3, v49, v50 offset0:40 offset1:106
	ds_write2_b32 v3, v51, v52 offset0:172 offset1:238
	v_add_u32_e32 v3, 0x1800, v30
	ds_write2_b32 v3, v53, v54 offset0:48 offset1:114
	ds_write2_b32 v3, v55, v56 offset0:180 offset1:246
	v_add_u32_e32 v3, 0x1c00, v30
	ds_write2_b32 v3, v57, v58 offset0:56 offset1:122
	ds_write2_b32 v3, v38, v2 offset0:188 offset1:254
	s_waitcnt lgkmcnt(0)
	ds_read2_b32 v[2:3], v0 offset1:33
	s_waitcnt lgkmcnt(0)
	v_cvt_pk_bf16_f32 v2, v2, v3
	ds_read2_b32 v[4:5], v0 offset0:66 offset1:99
	s_waitcnt lgkmcnt(0)
	v_cvt_pk_bf16_f32 v3, v4, v5
	ds_read2_b32 v[4:5], v0 offset0:132 offset1:165
	s_waitcnt lgkmcnt(0)
	v_cvt_pk_bf16_f32 v4, v4, v5
	ds_read2_b32 v[22:23], v0 offset0:198 offset1:231
	s_waitcnt lgkmcnt(0)
	v_cvt_pk_bf16_f32 v5, v22, v23
	v_add_u32_e32 v22, s4, v25
	s_ashr_i32 s37, s36, 31
	v_ashrrev_i32_e32 v23, 31, v22
	v_lshl_add_u64 v[20:21], s[36:37], 1, v[18:19]
	v_lshlrev_b64 v[34:35], 11, v[22:23]
	v_lshl_add_u64 v[34:35], v[20:21], 0, v[34:35]
	global_store_dwordx4 v[34:35], v[2:5], off
	ds_read2_b32 v[2:3], v0 offset0:8 offset1:41
	s_add_i32 s18, s18, s3
	s_waitcnt lgkmcnt(0)
	v_cvt_pk_bf16_f32 v2, v2, v3
	ds_read2_b32 v[4:5], v0 offset0:74 offset1:107
	s_waitcnt lgkmcnt(0)
	v_cvt_pk_bf16_f32 v3, v4, v5
	ds_read2_b32 v[4:5], v0 offset0:140 offset1:173
	s_waitcnt lgkmcnt(0)
	v_cvt_pk_bf16_f32 v4, v4, v5
	ds_read2_b32 v[34:35], v0 offset0:206 offset1:239
	s_waitcnt lgkmcnt(0)
	v_cvt_pk_bf16_f32 v5, v34, v35
	v_add_u32_e32 v34, 8, v22
	v_ashrrev_i32_e32 v35, 31, v34
	v_lshlrev_b64 v[34:35], 11, v[34:35]
	v_lshl_add_u64 v[34:35], v[20:21], 0, v[34:35]
	global_store_dwordx4 v[34:35], v[2:5], off
	ds_read2_b32 v[2:3], v0 offset0:16 offset1:49
	s_add_i32 s6, s6, s7
	s_waitcnt lgkmcnt(0)
	v_cvt_pk_bf16_f32 v2, v2, v3
	ds_read2_b32 v[4:5], v0 offset0:82 offset1:115
	s_waitcnt lgkmcnt(0)
	v_cvt_pk_bf16_f32 v3, v4, v5
	ds_read2_b32 v[4:5], v0 offset0:148 offset1:181
	s_waitcnt lgkmcnt(0)
	v_cvt_pk_bf16_f32 v4, v4, v5
	ds_read2_b32 v[34:35], v0 offset0:214 offset1:247
	s_waitcnt lgkmcnt(0)
	v_cvt_pk_bf16_f32 v5, v34, v35
	v_add_u32_e32 v34, 16, v22
	v_ashrrev_i32_e32 v35, 31, v34
	v_lshlrev_b64 v[34:35], 11, v[34:35]
	v_lshl_add_u64 v[34:35], v[20:21], 0, v[34:35]
	global_store_dwordx4 v[34:35], v[2:5], off
	v_add_u32_e32 v22, 24, v22
	ds_read2_b32 v[2:3], v0 offset0:24 offset1:57
	v_ashrrev_i32_e32 v23, 31, v22
	s_waitcnt lgkmcnt(0)
	v_cvt_pk_bf16_f32 v2, v2, v3
	ds_read2_b32 v[4:5], v0 offset0:90 offset1:123
	v_lshlrev_b64 v[22:23], 11, v[22:23]
	s_waitcnt lgkmcnt(0)
	v_cvt_pk_bf16_f32 v3, v4, v5
	ds_read2_b32 v[4:5], v0 offset0:156 offset1:189
	v_lshl_add_u64 v[20:21], v[20:21], 0, v[22:23]
	s_waitcnt lgkmcnt(0)
	v_cvt_pk_bf16_f32 v4, v4, v5
	ds_read2_b32 v[34:35], v0 offset0:222 offset1:255
	s_waitcnt lgkmcnt(0)
	v_cvt_pk_bf16_f32 v5, v34, v35
	global_store_dwordx4 v[20:21], v[2:5], off
	s_waitcnt lgkmcnt(0)
	s_cmpk_gt_i32 s18, 0xc4f
	s_cbranch_scc0 .LBB0_1484
	v_mov_b32_e32 v30, v32
	v_mov_b32_e32 v0, v14
	v_mov_b32_e32 v31, v25

; #define LAS __attribute__((address_space(3)))
; __device__ __forceinline__ void p0_transpose_item(const float* W, int K, int N, bf16_t* WT, LAS float* scr, int item, int lane) {
;     const int nblk = N / 32, kb = item / nblk, nb = item % nblk, k0 = 64 * kb, n0 = 32 * nb;
;     float tv[32];
; #pragma unroll
;     for (int i = 0; i < 32; ++i) tv[i] = W[(size_t)(k0 + 2 * i + (lane >> 5)) * N + n0 + (lane & 31)];
.LBB0_1490:
	s_ashr_i32 s14, s18, 31
	s_lshr_b32 s14, s14, 27
	s_add_i32 s14, s18, s14
	s_ashr_i32 s14, s14, 5
	s_lshl_b32 s40, s14, 6
	s_lshl_b32 s14, s14, 10
	v_or_b32_e32 v4, s40, v30
	s_sub_i32 s36, s6, s14
	v_or_b32_e32 v36, 2, v4
	s_ashr_i32 s37, s36, 31
	v_ashrrev_i32_e32 v5, 31, v4
	v_ashrrev_i32_e32 v37, 31, v36
	v_lshl_add_u64 v[2:3], s[36:37], 2, v[20:21]
	v_lshlrev_b64 v[24:25], 12, v[4:5]
	v_lshlrev_b64 v[36:37], 12, v[36:37]
	v_lshl_add_u64 v[24:25], v[2:3], 0, v[24:25]
	v_lshl_add_u64 v[36:37], v[2:3], 0, v[36:37]
	global_load_dword v24, v[24:25], off
	v_or_b32_e32 v38, 6, v4
	global_load_dword v25, v[36:37], off
	v_or_b32_e32 v36, 4, v4
	v_ashrrev_i32_e32 v37, 31, v36
	v_ashrrev_i32_e32 v39, 31, v38
	v_lshlrev_b64 v[36:37], 12, v[36:37]
	v_lshlrev_b64 v[38:39], 12, v[38:39]
	v_lshl_add_u64 v[36:37], v[2:3], 0, v[36:37]
	v_lshl_add_u64 v[38:39], v[2:3], 0, v[38:39]
	global_load_dword v36, v[36:37], off
	v_or_b32_e32 v40, 10, v4
	global_load_dword v37, v[38:39], off
	v_or_b32_e32 v38, 8, v4
	v_ashrrev_i32_e32 v39, 31, v38
	v_ashrrev_i32_e32 v41, 31, v40
	v_lshlrev_b64 v[38:39], 12, v[38:39]
	v_lshlrev_b64 v[40:41], 12, v[40:41]
	v_lshl_add_u64 v[38:39], v[2:3], 0, v[38:39]
	v_lshl_add_u64 v[40:41], v[2:3], 0, v[40:41]
	global_load_dword v38, v[38:39], off
	v_or_b32_e32 v42, 14, v4
	global_load_dword v39, v[40:41], off
	v_or_b32_e32 v40, 12, v4
	v_ashrrev_i32_e32 v41, 31, v40
	v_ashrrev_i32_e32 v43, 31, v42
	v_lshlrev_b64 v[40:41], 12, v[40:41]
	v_lshlrev_b64 v[42:43], 12, v[42:43]
	v_lshl_add_u64 v[40:41], v[2:3], 0, v[40:41]
	v_lshl_add_u64 v[42:43], v[2:3], 0, v[42:43]
	global_load_dword v40, v[40:41], off
	v_or_b32_e32 v44, 18, v4
	global_load_dword v41, v[42:43], off
	v_or_b32_e32 v42, 16, v4
	v_ashrrev_i32_e32 v43, 31, v42
	v_ashrrev_i32_e32 v45, 31, v44
	v_lshlrev_b64 v[42:43], 12, v[42:43]
	v_lshlrev_b64 v[44:45], 12, v[44:45]
	v_lshl_add_u64 v[42:43], v[2:3], 0, v[42:43]
	v_lshl_add_u64 v[44:45], v[2:3], 0, v[44:45]
	global_load_dword v42, v[42:43], off
	v_or_b32_e32 v46, 22, v4
	global_load_dword v43, v[44:45], off
	v_or_b32_e32 v44, 20, v4
	v_ashrrev_i32_e32 v45, 31, v44
	v_ashrrev_i32_e32 v47, 31, v46
	v_lshlrev_b64 v[44:45], 12, v[44:45]
	v_lshlrev_b64 v[46:47], 12, v[46:47]
	v_lshl_add_u64 v[44:45], v[2:3], 0, v[44:45]
	v_lshl_add_u64 v[46:47], v[2:3], 0, v[46:47]
	global_load_dword v44, v[44:45], off
	v_or_b32_e32 v48, 26, v4
	global_load_dword v45, v[46:47], off
	v_or_b32_e32 v46, 24, v4
	v_ashrrev_i32_e32 v47, 31, v46
	v_ashrrev_i32_e32 v49, 31, v48
	v_lshlrev_b64 v[46:47], 12, v[46:47]
	v_lshlrev_b64 v[48:49], 12, v[48:49]
	v_lshl_add_u64 v[46:47], v[2:3], 0, v[46:47]
	v_lshl_add_u64 v[48:49], v[2:3], 0, v[48:49]
	global_load_dword v46, v[46:47], off
	v_or_b32_e32 v50, 30, v4
	global_load_dword v47, v[48:49], off
	v_or_b32_e32 v48, 28, v4
	v_ashrrev_i32_e32 v49, 31, v48
	v_ashrrev_i32_e32 v51, 31, v50
	v_lshlrev_b64 v[48:49], 12, v[48:49]
	v_lshlrev_b64 v[50:51], 12, v[50:51]
	v_lshl_add_u64 v[48:49], v[2:3], 0, v[48:49]
	v_lshl_add_u64 v[50:51], v[2:3], 0, v[50:51]
	global_load_dword v48, v[48:49], off
	v_or_b32_e32 v52, 34, v4
	global_load_dword v49, v[50:51], off
	v_or_b32_e32 v50, 32, v4
	v_ashrrev_i32_e32 v51, 31, v50
	v_ashrrev_i32_e32 v53, 31, v52
	v_lshlrev_b64 v[50:51], 12, v[50:51]
	v_lshlrev_b64 v[52:53], 12, v[52:53]
	v_lshl_add_u64 v[50:51], v[2:3], 0, v[50:51]
	v_lshl_add_u64 v[52:53], v[2:3], 0, v[52:53]
	global_load_dword v50, v[50:51], off
	v_or_b32_e32 v54, 38, v4
	global_load_dword v51, v[52:53], off
	v_or_b32_e32 v52, 36, v4
	v_ashrrev_i32_e32 v53, 31, v52
	v_ashrrev_i32_e32 v55, 31, v54
	v_lshlrev_b64 v[52:53], 12, v[52:53]
	v_lshlrev_b64 v[54:55], 12, v[54:55]
	v_lshl_add_u64 v[52:53], v[2:3], 0, v[52:53]
	v_lshl_add_u64 v[54:55], v[2:3], 0, v[54:55]
	global_load_dword v52, v[52:53], off
	v_or_b32_e32 v56, 42, v4
	global_load_dword v53, v[54:55], off
	v_or_b32_e32 v54, 40, v4
	v_ashrrev_i32_e32 v55, 31, v54
	v_ashrrev_i32_e32 v57, 31, v56
	v_lshlrev_b64 v[54:55], 12, v[54:55]
	v_lshlrev_b64 v[56:57], 12, v[56:57]
	v_lshl_add_u64 v[54:55], v[2:3], 0, v[54:55]
	v_lshl_add_u64 v[56:57], v[2:3], 0, v[56:57]
	global_load_dword v54, v[54:55], off
	v_or_b32_e32 v58, 46, v4
	global_load_dword v55, v[56:57], off
	v_or_b32_e32 v56, 44, v4
	v_ashrrev_i32_e32 v57, 31, v56
	v_ashrrev_i32_e32 v59, 31, v58
	v_lshlrev_b64 v[56:57], 12, v[56:57]
	v_lshlrev_b64 v[58:59], 12, v[58:59]
	v_lshl_add_u64 v[56:57], v[2:3], 0, v[56:57]
	v_lshl_add_u64 v[58:59], v[2:3], 0, v[58:59]
	global_load_dword v56, v[56:57], off
	v_or_b32_e32 v60, 50, v4
	global_load_dword v57, v[58:59], off
	v_or_b32_e32 v58, 48, v4
	v_ashrrev_i32_e32 v59, 31, v58
	v_ashrrev_i32_e32 v61, 31, v60
	v_lshlrev_b64 v[58:59], 12, v[58:59]
	v_lshlrev_b64 v[60:61], 12, v[60:61]
	v_lshl_add_u64 v[58:59], v[2:3], 0, v[58:59]
	v_lshl_add_u64 v[60:61], v[2:3], 0, v[60:61]
	global_load_dword v58, v[58:59], off
	v_or_b32_e32 v62, 54, v4
	global_load_dword v59, v[60:61], off
	v_or_b32_e32 v60, 52, v4
	v_ashrrev_i32_e32 v61, 31, v60
	v_ashrrev_i32_e32 v63, 31, v62
	v_lshlrev_b64 v[60:61], 12, v[60:61]
	v_lshlrev_b64 v[62:63], 12, v[62:63]
	v_lshl_add_u64 v[60:61], v[2:3], 0, v[60:61]
	v_lshl_add_u64 v[62:63], v[2:3], 0, v[62:63]
	global_load_dword v60, v[60:61], off
	v_or_b32_e32 v64, 58, v4
	global_load_dword v61, v[62:63], off
	v_or_b32_e32 v62, 56, v4
	v_ashrrev_i32_e32 v63, 31, v62
	v_ashrrev_i32_e32 v65, 31, v64
	v_lshlrev_b64 v[62:63], 12, v[62:63]
	v_lshlrev_b64 v[64:65], 12, v[64:65]
	v_lshl_add_u64 v[62:63], v[2:3], 0, v[62:63]
	v_lshl_add_u64 v[64:65], v[2:3], 0, v[64:65]
	global_load_dword v62, v[62:63], off
	s_ashr_i32 s41, s40, 31
	global_load_dword v63, v[64:65], off
	v_or_b32_e32 v64, 60, v4
	v_or_b32_e32 v4, 62, v4
	v_ashrrev_i32_e32 v65, 31, v64
	v_ashrrev_i32_e32 v5, 31, v4
	v_lshlrev_b64 v[64:65], 12, v[64:65]
	v_lshlrev_b64 v[4:5], 12, v[4:5]
	v_lshl_add_u64 v[64:65], v[2:3], 0, v[64:65]
	v_lshl_add_u64 v[2:3], v[2:3], 0, v[4:5]
	global_load_dword v64, v[64:65], off
	s_add_i32 s18, s18, s3
	global_load_dword v2, v[2:3], off
	v_add_u32_e32 v3, 0x400, v0
	s_waitcnt vmcnt(0)
; #define LAS __attribute__((address_space(3)))
; __device__ __forceinline__ unsigned cvt_pk_bf16(float lo, float hi) { unsigned r; asm volatile("v_cvt_pk_bf16_f32 %0, %1, %2" : "=v"(r) : "v"(lo), "v"(hi)); return r; }
; __device__ __forceinline__ void p0_transpose_item(const float* W, int K, int N, bf16_t* WT, LAS float* scr, int item, int lane) {
;     ...
; #pragma unroll
;     for (int i = 0; i < 32; ++i) scr[(2 * i + (lane >> 5)) * 33 + (lane & 31)] = tv[i];
;     asm volatile("s_waitcnt lgkmcnt(0)" ::: "memory");
;     const int c = lane & 7;
; #pragma unroll
;     for (int j = 0; j < 4; ++j) { const int n = (lane >> 3) + 8 * j; const LAS float* s = scr + (8 * c) * 33 + n;
;         u32x4 o; o.x = cvt_pk_bf16(s[0 * 33], s[1 * 33]); o.y = cvt_pk_bf16(s[2 * 33], s[3 * 33]); o.z = cvt_pk_bf16(s[4 * 33], s[5 * 33]); o.w = cvt_pk_bf16(s[6 * 33], s[7 * 33]);
;         *(u32x4*)(WT + (size_t)(n0 + n) * K + k0 + 8 * c) = o; }
;     asm volatile("s_waitcnt lgkmcnt(0)" ::: "memory");
	ds_write2_b32 v0, v24, v25 offset1:66
	ds_write2_b32 v0, v36, v37 offset0:132 offset1:198
	ds_write2_b32 v3, v38, v39 offset0:8 offset1:74
	ds_write2_b32 v3, v40, v41 offset0:140 offset1:206
	v_add_u32_e32 v3, 0x800, v0
	ds_write2_b32 v3, v42, v43 offset0:16 offset1:82
	ds_write2_b32 v3, v44, v45 offset0:148 offset1:214
	v_add_u32_e32 v3, 0xc00, v0
	ds_write2_b32 v3, v46, v47 offset0:24 offset1:90
	ds_write2_b32 v3, v48, v49 offset0:156 offset1:222
	v_add_u32_e32 v3, 0x1000, v0
	ds_write2_b32 v3, v50, v51 offset0:32 offset1:98
	ds_write2_b32 v3, v52, v53 offset0:164 offset1:230
	v_add_u32_e32 v3, 0x1400, v0
	ds_write2_b32 v3, v54, v55 offset0:40 offset1:106
	ds_write2_b32 v3, v56, v57 offset0:172 offset1:238
	v_add_u32_e32 v3, 0x1800, v0
	ds_write2_b32 v3, v58, v59 offset0:48 offset1:114
	ds_write2_b32 v3, v60, v61 offset0:180 offset1:246
	v_add_u32_e32 v3, 0x1c00, v0
	ds_write2_b32 v3, v62, v63 offset0:56 offset1:122
	ds_write2_b32 v3, v64, v2 offset0:188 offset1:254
	s_waitcnt lgkmcnt(0)
	ds_read2_b32 v[2:3], v32 offset1:33
	s_waitcnt lgkmcnt(0)
	v_cvt_pk_bf16_f32 v2, v2, v3
	ds_read2_b32 v[4:5], v32 offset0:66 offset1:99
	s_waitcnt lgkmcnt(0)
	v_cvt_pk_bf16_f32 v3, v4, v5
	ds_read2_b32 v[4:5], v32 offset0:132 offset1:165
	s_waitcnt lgkmcnt(0)
	v_cvt_pk_bf16_f32 v4, v4, v5
	ds_read2_b32 v[36:37], v32 offset0:198 offset1:231
	s_waitcnt lgkmcnt(0)
	v_cvt_pk_bf16_f32 v5, v36, v37
	v_add_u32_e32 v36, s36, v31
	v_ashrrev_i32_e32 v37, 31, v36
	v_lshl_add_u64 v[24:25], s[40:41], 1, v[22:23]
	v_lshlrev_b64 v[36:37], 9, v[36:37]
	v_lshl_add_u64 v[36:37], v[24:25], 0, v[36:37]
	global_store_dwordx4 v[36:37], v[2:5], off
	ds_read2_b32 v[2:3], v33 offset1:33
	s_add_i32 s6, s6, s7
	s_waitcnt lgkmcnt(0)
	v_cvt_pk_bf16_f32 v2, v2, v3
	ds_read2_b32 v[4:5], v33 offset0:66 offset1:99
	s_waitcnt lgkmcnt(0)
	v_cvt_pk_bf16_f32 v3, v4, v5
	ds_read2_b32 v[4:5], v33 offset0:132 offset1:165
	s_waitcnt lgkmcnt(0)
	v_cvt_pk_bf16_f32 v4, v4, v5
	ds_read2_b32 v[36:37], v33 offset0:198 offset1:231
	s_waitcnt lgkmcnt(0)
	v_cvt_pk_bf16_f32 v5, v36, v37
	v_add_u32_e32 v36, s36, v27
	v_ashrrev_i32_e32 v37, 31, v36
	v_lshlrev_b64 v[36:37], 9, v[36:37]
	v_lshl_add_u64 v[36:37], v[24:25], 0, v[36:37]
	global_store_dwordx4 v[36:37], v[2:5], off
	ds_read2_b32 v[2:3], v34 offset1:33
	s_cmpk_gt_i32 s18, 0x7f
	s_waitcnt lgkmcnt(0)
	v_cvt_pk_bf16_f32 v2, v2, v3
	ds_read2_b32 v[4:5], v34 offset0:66 offset1:99
	s_waitcnt lgkmcnt(0)
	v_cvt_pk_bf16_f32 v3, v4, v5
	ds_read2_b32 v[4:5], v34 offset0:132 offset1:165
	s_waitcnt lgkmcnt(0)
	v_cvt_pk_bf16_f32 v4, v4, v5
	ds_read2_b32 v[36:37], v34 offset0:198 offset1:231
	s_waitcnt lgkmcnt(0)
	v_cvt_pk_bf16_f32 v5, v36, v37
	v_add_u32_e32 v36, s36, v28
	v_ashrrev_i32_e32 v37, 31, v36
	v_lshlrev_b64 v[36:37], 9, v[36:37]
	v_lshl_add_u64 v[36:37], v[24:25], 0, v[36:37]
	global_store_dwordx4 v[36:37], v[2:5], off
	ds_read2_b32 v[2:3], v35 offset1:33
	s_waitcnt lgkmcnt(0)
	v_cvt_pk_bf16_f32 v2, v2, v3
	ds_read2_b32 v[4:5], v35 offset0:66 offset1:99
	s_waitcnt lgkmcnt(0)
	v_cvt_pk_bf16_f32 v3, v4, v5
	ds_read2_b32 v[4:5], v35 offset0:132 offset1:165
	s_waitcnt lgkmcnt(0)
	v_cvt_pk_bf16_f32 v4, v4, v5
	ds_read2_b32 v[36:37], v35 offset0:198 offset1:231
	s_waitcnt lgkmcnt(0)
	v_cvt_pk_bf16_f32 v5, v36, v37
	v_add_u32_e32 v36, s36, v29
	v_ashrrev_i32_e32 v37, 31, v36
	v_lshlrev_b64 v[36:37], 9, v[36:37]
	v_lshl_add_u64 v[24:25], v[24:25], 0, v[36:37]
	global_store_dwordx4 v[24:25], v[2:5], off
	s_waitcnt lgkmcnt(0)
	s_cbranch_scc0 .LBB0_1490
	s_branch .LBB0_1487

; #define LAS __attribute__((address_space(3)))
; __device__ __forceinline__ void p0_transpose_item(const float* W, int K, int N, bf16_t* WT, LAS float* scr, int item, int lane) {
;     const int nblk = N / 32, kb = item / nblk, nb = item % nblk, k0 = 64 * kb, n0 = 32 * nb;
;     float tv[32];
; #pragma unroll
;     for (int i = 0; i < 32; ++i) tv[i] = W[(size_t)(k0 + 2 * i + (lane >> 5)) * N + n0 + (lane & 31)];
.LBB0_1493:
	s_ashr_i32 s4, s7, 31
	s_lshr_b32 s4, s4, 27
	s_add_i32 s4, s7, s4
	s_ashr_i32 s4, s4, 5
	s_lshl_b32 s36, s4, 6
	s_lshl_b32 s4, s4, 10
	v_or_b32_e32 v4, s36, v30
	s_sub_i32 s4, s1, s4
	v_or_b32_e32 v22, 2, v4
	s_ashr_i32 s5, s4, 31
	v_ashrrev_i32_e32 v5, 31, v4
	v_ashrrev_i32_e32 v23, 31, v22
	v_lshl_add_u64 v[2:3], s[4:5], 2, v[16:17]
	v_lshlrev_b64 v[20:21], 12, v[4:5]
	v_lshlrev_b64 v[22:23], 12, v[22:23]
	v_lshl_add_u64 v[20:21], v[2:3], 0, v[20:21]
	v_lshl_add_u64 v[22:23], v[2:3], 0, v[22:23]
	global_load_dword v20, v[20:21], off
	v_or_b32_e32 v24, 6, v4
	global_load_dword v21, v[22:23], off
	v_or_b32_e32 v22, 4, v4
	v_ashrrev_i32_e32 v23, 31, v22
	v_ashrrev_i32_e32 v25, 31, v24
	v_lshlrev_b64 v[22:23], 12, v[22:23]
	v_lshlrev_b64 v[24:25], 12, v[24:25]
	v_lshl_add_u64 v[22:23], v[2:3], 0, v[22:23]
	v_lshl_add_u64 v[24:25], v[2:3], 0, v[24:25]
	global_load_dword v22, v[22:23], off
	v_or_b32_e32 v36, 10, v4
	global_load_dword v23, v[24:25], off
	v_or_b32_e32 v24, 8, v4
	v_ashrrev_i32_e32 v25, 31, v24
	v_ashrrev_i32_e32 v37, 31, v36
	v_lshlrev_b64 v[24:25], 12, v[24:25]
	v_lshlrev_b64 v[36:37], 12, v[36:37]
	v_lshl_add_u64 v[24:25], v[2:3], 0, v[24:25]
	v_lshl_add_u64 v[36:37], v[2:3], 0, v[36:37]
	global_load_dword v24, v[24:25], off
	v_or_b32_e32 v38, 14, v4
	global_load_dword v25, v[36:37], off
	v_or_b32_e32 v36, 12, v4
	v_ashrrev_i32_e32 v37, 31, v36
	v_ashrrev_i32_e32 v39, 31, v38
	v_lshlrev_b64 v[36:37], 12, v[36:37]
	v_lshlrev_b64 v[38:39], 12, v[38:39]
	v_lshl_add_u64 v[36:37], v[2:3], 0, v[36:37]
	v_lshl_add_u64 v[38:39], v[2:3], 0, v[38:39]
	global_load_dword v36, v[36:37], off
	v_or_b32_e32 v40, 18, v4
	global_load_dword v37, v[38:39], off
	v_or_b32_e32 v38, 16, v4
	v_ashrrev_i32_e32 v39, 31, v38
	v_ashrrev_i32_e32 v41, 31, v40
	v_lshlrev_b64 v[38:39], 12, v[38:39]
	v_lshlrev_b64 v[40:41], 12, v[40:41]
	v_lshl_add_u64 v[38:39], v[2:3], 0, v[38:39]
	v_lshl_add_u64 v[40:41], v[2:3], 0, v[40:41]
	global_load_dword v38, v[38:39], off
	v_or_b32_e32 v42, 22, v4
	global_load_dword v39, v[40:41], off
	v_or_b32_e32 v40, 20, v4
	v_ashrrev_i32_e32 v41, 31, v40
	v_ashrrev_i32_e32 v43, 31, v42
	v_lshlrev_b64 v[40:41], 12, v[40:41]
	v_lshlrev_b64 v[42:43], 12, v[42:43]
	v_lshl_add_u64 v[40:41], v[2:3], 0, v[40:41]
	v_lshl_add_u64 v[42:43], v[2:3], 0, v[42:43]
	global_load_dword v40, v[40:41], off
	v_or_b32_e32 v44, 26, v4
	global_load_dword v41, v[42:43], off
	v_or_b32_e32 v42, 24, v4
	v_ashrrev_i32_e32 v43, 31, v42
	v_ashrrev_i32_e32 v45, 31, v44
	v_lshlrev_b64 v[42:43], 12, v[42:43]
	v_lshlrev_b64 v[44:45], 12, v[44:45]
	v_lshl_add_u64 v[42:43], v[2:3], 0, v[42:43]
	v_lshl_add_u64 v[44:45], v[2:3], 0, v[44:45]
	global_load_dword v42, v[42:43], off
	v_or_b32_e32 v46, 30, v4
	global_load_dword v43, v[44:45], off
	v_or_b32_e32 v44, 28, v4
	v_ashrrev_i32_e32 v45, 31, v44
	v_ashrrev_i32_e32 v47, 31, v46
	v_lshlrev_b64 v[44:45], 12, v[44:45]
	v_lshlrev_b64 v[46:47], 12, v[46:47]
	v_lshl_add_u64 v[44:45], v[2:3], 0, v[44:45]
	v_lshl_add_u64 v[46:47], v[2:3], 0, v[46:47]
	global_load_dword v44, v[44:45], off
	v_or_b32_e32 v48, 34, v4
	global_load_dword v45, v[46:47], off
	v_or_b32_e32 v46, 32, v4
	v_ashrrev_i32_e32 v47, 31, v46
	v_ashrrev_i32_e32 v49, 31, v48
	v_lshlrev_b64 v[46:47], 12, v[46:47]
	v_lshlrev_b64 v[48:49], 12, v[48:49]
	v_lshl_add_u64 v[46:47], v[2:3], 0, v[46:47]
	v_lshl_add_u64 v[48:49], v[2:3], 0, v[48:49]
	global_load_dword v46, v[46:47], off
	v_or_b32_e32 v50, 38, v4
	global_load_dword v47, v[48:49], off
	v_or_b32_e32 v48, 36, v4
	v_ashrrev_i32_e32 v49, 31, v48
	v_ashrrev_i32_e32 v51, 31, v50
	v_lshlrev_b64 v[48:49], 12, v[48:49]
	v_lshlrev_b64 v[50:51], 12, v[50:51]
	v_lshl_add_u64 v[48:49], v[2:3], 0, v[48:49]
	v_lshl_add_u64 v[50:51], v[2:3], 0, v[50:51]
	global_load_dword v48, v[48:49], off
	v_or_b32_e32 v52, 42, v4
	global_load_dword v49, v[50:51], off
	v_or_b32_e32 v50, 40, v4
	v_ashrrev_i32_e32 v51, 31, v50
	v_ashrrev_i32_e32 v53, 31, v52
	v_lshlrev_b64 v[50:51], 12, v[50:51]
	v_lshlrev_b64 v[52:53], 12, v[52:53]
	v_lshl_add_u64 v[50:51], v[2:3], 0, v[50:51]
	v_lshl_add_u64 v[52:53], v[2:3], 0, v[52:53]
	global_load_dword v50, v[50:51], off
	v_or_b32_e32 v54, 46, v4
	global_load_dword v51, v[52:53], off
	v_or_b32_e32 v52, 44, v4
	v_ashrrev_i32_e32 v53, 31, v52
	v_ashrrev_i32_e32 v55, 31, v54
	v_lshlrev_b64 v[52:53], 12, v[52:53]
	v_lshlrev_b64 v[54:55], 12, v[54:55]
	v_lshl_add_u64 v[52:53], v[2:3], 0, v[52:53]
	v_lshl_add_u64 v[54:55], v[2:3], 0, v[54:55]
	global_load_dword v52, v[52:53], off
	v_or_b32_e32 v56, 50, v4
	global_load_dword v53, v[54:55], off
	v_or_b32_e32 v54, 48, v4
	v_ashrrev_i32_e32 v55, 31, v54
	v_ashrrev_i32_e32 v57, 31, v56
	v_lshlrev_b64 v[54:55], 12, v[54:55]
	v_lshlrev_b64 v[56:57], 12, v[56:57]
	v_lshl_add_u64 v[54:55], v[2:3], 0, v[54:55]
	v_lshl_add_u64 v[56:57], v[2:3], 0, v[56:57]
	global_load_dword v54, v[54:55], off
	v_or_b32_e32 v58, 54, v4
	global_load_dword v55, v[56:57], off
	v_or_b32_e32 v56, 52, v4
	v_ashrrev_i32_e32 v57, 31, v56
	v_ashrrev_i32_e32 v59, 31, v58
	v_lshlrev_b64 v[56:57], 12, v[56:57]
	v_lshlrev_b64 v[58:59], 12, v[58:59]
	v_lshl_add_u64 v[56:57], v[2:3], 0, v[56:57]
	v_lshl_add_u64 v[58:59], v[2:3], 0, v[58:59]
	global_load_dword v56, v[56:57], off
	v_or_b32_e32 v60, 58, v4
	global_load_dword v57, v[58:59], off
	v_or_b32_e32 v58, 56, v4
	v_ashrrev_i32_e32 v59, 31, v58
	v_ashrrev_i32_e32 v61, 31, v60
	v_lshlrev_b64 v[58:59], 12, v[58:59]
	v_lshlrev_b64 v[60:61], 12, v[60:61]
	v_lshl_add_u64 v[58:59], v[2:3], 0, v[58:59]
	v_lshl_add_u64 v[60:61], v[2:3], 0, v[60:61]
	global_load_dword v58, v[58:59], off
	s_ashr_i32 s37, s36, 31
	global_load_dword v59, v[60:61], off
	v_or_b32_e32 v60, 60, v4
	v_or_b32_e32 v4, 62, v4
	v_ashrrev_i32_e32 v61, 31, v60
	v_ashrrev_i32_e32 v5, 31, v4
	v_lshlrev_b64 v[60:61], 12, v[60:61]
	v_lshlrev_b64 v[4:5], 12, v[4:5]
	v_lshl_add_u64 v[60:61], v[2:3], 0, v[60:61]
	v_lshl_add_u64 v[2:3], v[2:3], 0, v[4:5]
	global_load_dword v60, v[60:61], off
	s_add_i32 s7, s7, s3
	global_load_dword v2, v[2:3], off
	v_add_u32_e32 v3, 0x400, v0
	s_waitcnt vmcnt(0)
; #define LAS __attribute__((address_space(3)))
; __device__ __forceinline__ unsigned cvt_pk_bf16(float lo, float hi) { unsigned r; asm volatile("v_cvt_pk_bf16_f32 %0, %1, %2" : "=v"(r) : "v"(lo), "v"(hi)); return r; }
; __device__ __forceinline__ void p0_transpose_item(const float* W, int K, int N, bf16_t* WT, LAS float* scr, int item, int lane) {
;     ...
; #pragma unroll
;     for (int i = 0; i < 32; ++i) scr[(2 * i + (lane >> 5)) * 33 + (lane & 31)] = tv[i];
;     asm volatile("s_waitcnt lgkmcnt(0)" ::: "memory");
;     const int c = lane & 7;
; #pragma unroll
;     for (int j = 0; j < 4; ++j) { const int n = (lane >> 3) + 8 * j; const LAS float* s = scr + (8 * c) * 33 + n;
;         u32x4 o; o.x = cvt_pk_bf16(s[0 * 33], s[1 * 33]); o.y = cvt_pk_bf16(s[2 * 33], s[3 * 33]); o.z = cvt_pk_bf16(s[4 * 33], s[5 * 33]); o.w = cvt_pk_bf16(s[6 * 33], s[7 * 33]);
;         *(u32x4*)(WT + (size_t)(n0 + n) * K + k0 + 8 * c) = o; }
;     asm volatile("s_waitcnt lgkmcnt(0)" ::: "memory");
	ds_write2_b32 v0, v20, v21 offset1:66
	ds_write2_b32 v0, v22, v23 offset0:132 offset1:198
	ds_write2_b32 v3, v24, v25 offset0:8 offset1:74
	ds_write2_b32 v3, v36, v37 offset0:140 offset1:206
	v_add_u32_e32 v3, 0x800, v0
	ds_write2_b32 v3, v38, v39 offset0:16 offset1:82
	ds_write2_b32 v3, v40, v41 offset0:148 offset1:214
	v_add_u32_e32 v3, 0xc00, v0
	ds_write2_b32 v3, v42, v43 offset0:24 offset1:90
	ds_write2_b32 v3, v44, v45 offset0:156 offset1:222
	v_add_u32_e32 v3, 0x1000, v0
	ds_write2_b32 v3, v46, v47 offset0:32 offset1:98
	ds_write2_b32 v3, v48, v49 offset0:164 offset1:230
	v_add_u32_e32 v3, 0x1400, v0
	ds_write2_b32 v3, v50, v51 offset0:40 offset1:106
	ds_write2_b32 v3, v52, v53 offset0:172 offset1:238
	v_add_u32_e32 v3, 0x1800, v0
	ds_write2_b32 v3, v54, v55 offset0:48 offset1:114
	ds_write2_b32 v3, v56, v57 offset0:180 offset1:246
	v_add_u32_e32 v3, 0x1c00, v0
	ds_write2_b32 v3, v58, v59 offset0:56 offset1:122
	ds_write2_b32 v3, v60, v2 offset0:188 offset1:254
	s_waitcnt lgkmcnt(0)
	ds_read2_b32 v[2:3], v32 offset1:33
	s_waitcnt lgkmcnt(0)
	v_cvt_pk_bf16_f32 v2, v2, v3
	ds_read2_b32 v[4:5], v32 offset0:66 offset1:99
	s_waitcnt lgkmcnt(0)
	v_cvt_pk_bf16_f32 v3, v4, v5
	ds_read2_b32 v[4:5], v32 offset0:132 offset1:165
	s_waitcnt lgkmcnt(0)
	v_cvt_pk_bf16_f32 v4, v4, v5
	ds_read2_b32 v[22:23], v32 offset0:198 offset1:231
	s_waitcnt lgkmcnt(0)
	v_cvt_pk_bf16_f32 v5, v22, v23
	v_add_u32_e32 v22, s4, v31
	v_ashrrev_i32_e32 v23, 31, v22
	v_lshl_add_u64 v[20:21], s[36:37], 1, v[18:19]
	v_lshlrev_b64 v[22:23], 11, v[22:23]
	v_lshl_add_u64 v[22:23], v[20:21], 0, v[22:23]
	global_store_dwordx4 v[22:23], v[2:5], off
	ds_read2_b32 v[2:3], v33 offset1:33
	s_add_i32 s1, s1, s6
	s_waitcnt lgkmcnt(0)
	v_cvt_pk_bf16_f32 v2, v2, v3
	ds_read2_b32 v[4:5], v33 offset0:66 offset1:99
	s_waitcnt lgkmcnt(0)
	v_cvt_pk_bf16_f32 v3, v4, v5
	ds_read2_b32 v[4:5], v33 offset0:132 offset1:165
	s_waitcnt lgkmcnt(0)
	v_cvt_pk_bf16_f32 v4, v4, v5
	ds_read2_b32 v[22:23], v33 offset0:198 offset1:231
	s_waitcnt lgkmcnt(0)
	v_cvt_pk_bf16_f32 v5, v22, v23
	v_add_u32_e32 v22, s4, v27
	v_ashrrev_i32_e32 v23, 31, v22
	v_lshlrev_b64 v[22:23], 11, v[22:23]
	v_lshl_add_u64 v[22:23], v[20:21], 0, v[22:23]
	global_store_dwordx4 v[22:23], v[2:5], off
	ds_read2_b32 v[2:3], v34 offset1:33
	s_cmpk_gt_i32 s7, 0x1ff
	s_waitcnt lgkmcnt(0)
	v_cvt_pk_bf16_f32 v2, v2, v3
	ds_read2_b32 v[4:5], v34 offset0:66 offset1:99
	s_waitcnt lgkmcnt(0)
	v_cvt_pk_bf16_f32 v3, v4, v5
	ds_read2_b32 v[4:5], v34 offset0:132 offset1:165
	s_waitcnt lgkmcnt(0)
	v_cvt_pk_bf16_f32 v4, v4, v5
	ds_read2_b32 v[22:23], v34 offset0:198 offset1:231
	s_waitcnt lgkmcnt(0)
	v_cvt_pk_bf16_f32 v5, v22, v23
	v_add_u32_e32 v22, s4, v28
	v_ashrrev_i32_e32 v23, 31, v22
	v_lshlrev_b64 v[22:23], 11, v[22:23]
	v_lshl_add_u64 v[22:23], v[20:21], 0, v[22:23]
	global_store_dwordx4 v[22:23], v[2:5], off
	ds_read2_b32 v[2:3], v35 offset1:33
	s_waitcnt lgkmcnt(0)
	v_cvt_pk_bf16_f32 v2, v2, v3
	ds_read2_b32 v[4:5], v35 offset0:66 offset1:99
	s_waitcnt lgkmcnt(0)
	v_cvt_pk_bf16_f32 v3, v4, v5
	ds_read2_b32 v[4:5], v35 offset0:132 offset1:165
	s_waitcnt lgkmcnt(0)
	v_cvt_pk_bf16_f32 v4, v4, v5
	ds_read2_b32 v[22:23], v35 offset0:198 offset1:231
	s_waitcnt lgkmcnt(0)
	v_cvt_pk_bf16_f32 v5, v22, v23
	v_add_u32_e32 v22, s4, v29
	v_ashrrev_i32_e32 v23, 31, v22
	v_lshlrev_b64 v[22:23], 11, v[22:23]
	v_lshl_add_u64 v[20:21], v[20:21], 0, v[22:23]
	global_store_dwordx4 v[20:21], v[2:5], off
	s_waitcnt lgkmcnt(0)
	s_cbranch_scc0 .LBB0_1493

; #define LAS __attribute__((address_space(3)))
; __device__ __forceinline__ void p0_transpose_item(const float* W, int K, int N, bf16_t* WT, LAS float* scr, int item, int lane) {
;     const int nblk = N / 32, kb = item / nblk, nb = item % nblk, k0 = 64 * kb, n0 = 32 * nb;
;     float tv[32];
; #pragma unroll
;     for (int i = 0; i < 32; ++i) tv[i] = W[(size_t)(k0 + 2 * i + (lane >> 5)) * N + n0 + (lane & 31)];
.LBB0_1496:
	s_mul_hi_i32 s4, s7, 0x2aaaaaab
	s_lshr_b32 s5, s4, 31
	s_ashr_i32 s4, s4, 1
	s_add_i32 s4, s4, s5
	s_lshl_b32 s36, s4, 6
	s_mulk_i32 s4, 0xfe80
	s_add_i32 s4, s1, s4
	s_ashr_i32 s5, s4, 31
	v_or_b32_e32 v42, s36, v30
	v_lshl_add_u64 v[2:3], s[4:5], 2, v[16:17]
	v_mad_i64_i32 v[4:5], s[14:15], v42, s18, v[2:3]
	global_load_dword v4, v[4:5], off
	v_or_b32_e32 v5, 2, v42
	v_mad_i64_i32 v[20:21], s[14:15], v5, s18, v[2:3]
	global_load_dword v5, v[20:21], off
	v_or_b32_e32 v20, 4, v42
	v_mad_i64_i32 v[20:21], s[14:15], v20, s18, v[2:3]
	global_load_dword v20, v[20:21], off
	v_or_b32_e32 v21, 6, v42
	v_mad_i64_i32 v[22:23], s[14:15], v21, s18, v[2:3]
	global_load_dword v21, v[22:23], off
	v_or_b32_e32 v22, 8, v42
	v_mad_i64_i32 v[22:23], s[14:15], v22, s18, v[2:3]
	global_load_dword v22, v[22:23], off
	v_or_b32_e32 v23, 10, v42
	v_mad_i64_i32 v[24:25], s[14:15], v23, s18, v[2:3]
	global_load_dword v23, v[24:25], off
	v_or_b32_e32 v24, 12, v42
	v_mad_i64_i32 v[24:25], s[14:15], v24, s18, v[2:3]
	global_load_dword v24, v[24:25], off
	v_or_b32_e32 v25, 14, v42
	v_mad_i64_i32 v[36:37], s[14:15], v25, s18, v[2:3]
	global_load_dword v25, v[36:37], off
	v_or_b32_e32 v36, 16, v42
	v_mad_i64_i32 v[36:37], s[14:15], v36, s18, v[2:3]
	global_load_dword v36, v[36:37], off
	v_or_b32_e32 v37, 18, v42
	v_mad_i64_i32 v[38:39], s[14:15], v37, s18, v[2:3]
	global_load_dword v37, v[38:39], off
	v_or_b32_e32 v38, 20, v42
	v_mad_i64_i32 v[38:39], s[14:15], v38, s18, v[2:3]
	global_load_dword v38, v[38:39], off
	v_or_b32_e32 v39, 22, v42
	v_mad_i64_i32 v[40:41], s[14:15], v39, s18, v[2:3]
	global_load_dword v39, v[40:41], off
	v_or_b32_e32 v40, 24, v42
	v_mad_i64_i32 v[40:41], s[14:15], v40, s18, v[2:3]
	global_load_dword v43, v[40:41], off
	v_or_b32_e32 v40, 26, v42
	v_mad_i64_i32 v[40:41], s[14:15], v40, s18, v[2:3]
	global_load_dword v44, v[40:41], off
	v_or_b32_e32 v40, 28, v42
	v_mad_i64_i32 v[40:41], s[14:15], v40, s18, v[2:3]
	global_load_dword v45, v[40:41], off
	v_or_b32_e32 v40, 30, v42
	v_mad_i64_i32 v[40:41], s[14:15], v40, s18, v[2:3]
	global_load_dword v46, v[40:41], off
	v_or_b32_e32 v40, 32, v42
	v_mad_i64_i32 v[40:41], s[14:15], v40, s18, v[2:3]
	global_load_dword v47, v[40:41], off
	v_or_b32_e32 v40, 34, v42
	v_mad_i64_i32 v[40:41], s[14:15], v40, s18, v[2:3]
	global_load_dword v48, v[40:41], off
	v_or_b32_e32 v40, 36, v42
	v_mad_i64_i32 v[40:41], s[14:15], v40, s18, v[2:3]
	global_load_dword v49, v[40:41], off
	v_or_b32_e32 v40, 38, v42
	v_mad_i64_i32 v[40:41], s[14:15], v40, s18, v[2:3]
	global_load_dword v50, v[40:41], off
	v_or_b32_e32 v40, 40, v42
	v_mad_i64_i32 v[40:41], s[14:15], v40, s18, v[2:3]
	global_load_dword v51, v[40:41], off
	v_or_b32_e32 v40, 42, v42
	v_mad_i64_i32 v[40:41], s[14:15], v40, s18, v[2:3]
	global_load_dword v52, v[40:41], off
	v_or_b32_e32 v40, 44, v42
	v_mad_i64_i32 v[40:41], s[14:15], v40, s18, v[2:3]
	global_load_dword v53, v[40:41], off
	v_or_b32_e32 v40, 46, v42
	v_mad_i64_i32 v[40:41], s[14:15], v40, s18, v[2:3]
	global_load_dword v54, v[40:41], off
	v_or_b32_e32 v40, 48, v42
	v_mad_i64_i32 v[40:41], s[14:15], v40, s18, v[2:3]
	global_load_dword v55, v[40:41], off
	v_or_b32_e32 v40, 50, v42
	v_mad_i64_i32 v[40:41], s[14:15], v40, s18, v[2:3]
	global_load_dword v56, v[40:41], off
	v_or_b32_e32 v40, 52, v42
	v_mad_i64_i32 v[40:41], s[14:15], v40, s18, v[2:3]
	global_load_dword v57, v[40:41], off
	v_or_b32_e32 v40, 54, v42
	v_mad_i64_i32 v[40:41], s[14:15], v40, s18, v[2:3]
	global_load_dword v58, v[40:41], off
	v_or_b32_e32 v40, 56, v42
	v_mad_i64_i32 v[40:41], s[14:15], v40, s18, v[2:3]
	global_load_dword v59, v[40:41], off
	v_or_b32_e32 v40, 58, v42
	v_mad_i64_i32 v[40:41], s[14:15], v40, s18, v[2:3]
	global_load_dword v60, v[40:41], off
	v_or_b32_e32 v40, 60, v42
	v_mad_i64_i32 v[40:41], s[14:15], v40, s18, v[2:3]
	global_load_dword v40, v[40:41], off
	v_or_b32_e32 v41, 62, v42
	v_mad_i64_i32 v[2:3], s[14:15], v41, s18, v[2:3]
	global_load_dword v2, v[2:3], off
	v_add_u32_e32 v3, 0x400, v0
	s_waitcnt vmcnt(0)
; #define LAS __attribute__((address_space(3)))
; __device__ __forceinline__ unsigned cvt_pk_bf16(float lo, float hi) { unsigned r; asm volatile("v_cvt_pk_bf16_f32 %0, %1, %2" : "=v"(r) : "v"(lo), "v"(hi)); return r; }
; __device__ __forceinline__ void p0_transpose_item(const float* W, int K, int N, bf16_t* WT, LAS float* scr, int item, int lane) {
;     ...
; #pragma unroll
;     for (int i = 0; i < 32; ++i) scr[(2 * i + (lane >> 5)) * 33 + (lane & 31)] = tv[i];
;     asm volatile("s_waitcnt lgkmcnt(0)" ::: "memory");
;     const int c = lane & 7;
; #pragma unroll
;     for (int j = 0; j < 4; ++j) { const int n = (lane >> 3) + 8 * j; const LAS float* s = scr + (8 * c) * 33 + n;
;         u32x4 o; o.x = cvt_pk_bf16(s[0 * 33], s[1 * 33]); o.y = cvt_pk_bf16(s[2 * 33], s[3 * 33]); o.z = cvt_pk_bf16(s[4 * 33], s[5 * 33]); o.w = cvt_pk_bf16(s[6 * 33], s[7 * 33]);
;         *(u32x4*)(WT + (size_t)(n0 + n) * K + k0 + 8 * c) = o; }
;     asm volatile("s_waitcnt lgkmcnt(0)" ::: "memory");
	ds_write2_b32 v0, v4, v5 offset1:66
	ds_write2_b32 v0, v20, v21 offset0:132 offset1:198
	ds_write2_b32 v3, v22, v23 offset0:8 offset1:74
	ds_write2_b32 v3, v24, v25 offset0:140 offset1:206
	v_add_u32_e32 v3, 0x800, v0
	ds_write2_b32 v3, v36, v37 offset0:16 offset1:82
	ds_write2_b32 v3, v38, v39 offset0:148 offset1:214
	v_add_u32_e32 v3, 0xc00, v0
	ds_write2_b32 v3, v43, v44 offset0:24 offset1:90
	ds_write2_b32 v3, v45, v46 offset0:156 offset1:222
	v_add_u32_e32 v3, 0x1000, v0
	ds_write2_b32 v3, v47, v48 offset0:32 offset1:98
	ds_write2_b32 v3, v49, v50 offset0:164 offset1:230
	v_add_u32_e32 v3, 0x1400, v0
	ds_write2_b32 v3, v51, v52 offset0:40 offset1:106
	ds_write2_b32 v3, v53, v54 offset0:172 offset1:238
	v_add_u32_e32 v3, 0x1800, v0
	ds_write2_b32 v3, v55, v56 offset0:48 offset1:114
	ds_write2_b32 v3, v57, v58 offset0:180 offset1:246
	v_add_u32_e32 v3, 0x1c00, v0
	ds_write2_b32 v3, v59, v60 offset0:56 offset1:122
	ds_write2_b32 v3, v40, v2 offset0:188 offset1:254
	s_waitcnt lgkmcnt(0)
	ds_read2_b32 v[2:3], v32 offset1:33
	s_waitcnt lgkmcnt(0)
	v_cvt_pk_bf16_f32 v2, v2, v3
	ds_read2_b32 v[4:5], v32 offset0:66 offset1:99
	s_waitcnt lgkmcnt(0)
	v_cvt_pk_bf16_f32 v3, v4, v5
	ds_read2_b32 v[4:5], v32 offset0:132 offset1:165
	s_waitcnt lgkmcnt(0)
	v_cvt_pk_bf16_f32 v4, v4, v5
	ds_read2_b32 v[22:23], v32 offset0:198 offset1:231
	s_waitcnt lgkmcnt(0)
	v_cvt_pk_bf16_f32 v5, v22, v23
	v_add_u32_e32 v22, s4, v31
	s_ashr_i32 s37, s36, 31
	v_ashrrev_i32_e32 v23, 31, v22
	v_lshl_add_u64 v[20:21], s[36:37], 1, v[18:19]
	v_lshlrev_b64 v[22:23], 9, v[22:23]
	v_lshl_add_u64 v[22:23], v[20:21], 0, v[22:23]
	global_store_dwordx4 v[22:23], v[2:5], off
	ds_read2_b32 v[2:3], v33 offset1:33
	s_add_i32 s7, s7, s3
	s_waitcnt lgkmcnt(0)
	v_cvt_pk_bf16_f32 v2, v2, v3
	ds_read2_b32 v[4:5], v33 offset0:66 offset1:99
	s_waitcnt lgkmcnt(0)
	v_cvt_pk_bf16_f32 v3, v4, v5
	ds_read2_b32 v[4:5], v33 offset0:132 offset1:165
	s_waitcnt lgkmcnt(0)
	v_cvt_pk_bf16_f32 v4, v4, v5
	ds_read2_b32 v[22:23], v33 offset0:198 offset1:231
	s_waitcnt lgkmcnt(0)
	v_cvt_pk_bf16_f32 v5, v22, v23
	v_add_u32_e32 v22, s4, v27
	v_ashrrev_i32_e32 v23, 31, v22
	v_lshlrev_b64 v[22:23], 9, v[22:23]
	v_lshl_add_u64 v[22:23], v[20:21], 0, v[22:23]
	global_store_dwordx4 v[22:23], v[2:5], off
	ds_read2_b32 v[2:3], v34 offset1:33
	s_add_i32 s1, s1, s6
	s_waitcnt lgkmcnt(0)
	v_cvt_pk_bf16_f32 v2, v2, v3
	ds_read2_b32 v[4:5], v34 offset0:66 offset1:99
	s_waitcnt lgkmcnt(0)
	v_cvt_pk_bf16_f32 v3, v4, v5
	ds_read2_b32 v[4:5], v34 offset0:132 offset1:165
	s_waitcnt lgkmcnt(0)
	v_cvt_pk_bf16_f32 v4, v4, v5
	ds_read2_b32 v[22:23], v34 offset0:198 offset1:231
	s_waitcnt lgkmcnt(0)
	v_cvt_pk_bf16_f32 v5, v22, v23
	v_add_u32_e32 v22, s4, v28
	v_ashrrev_i32_e32 v23, 31, v22
	v_lshlrev_b64 v[22:23], 9, v[22:23]
	v_lshl_add_u64 v[22:23], v[20:21], 0, v[22:23]
	global_store_dwordx4 v[22:23], v[2:5], off
	ds_read2_b32 v[2:3], v35 offset1:33
	s_cmp_gt_i32 s7, 47
	s_waitcnt lgkmcnt(0)
	v_cvt_pk_bf16_f32 v2, v2, v3
	ds_read2_b32 v[4:5], v35 offset0:66 offset1:99
	s_waitcnt lgkmcnt(0)
	v_cvt_pk_bf16_f32 v3, v4, v5
	ds_read2_b32 v[4:5], v35 offset0:132 offset1:165
	s_waitcnt lgkmcnt(0)
	v_cvt_pk_bf16_f32 v4, v4, v5
	ds_read2_b32 v[22:23], v35 offset0:198 offset1:231
	s_waitcnt lgkmcnt(0)
	v_cvt_pk_bf16_f32 v5, v22, v23
	v_add_u32_e32 v22, s4, v29
	v_ashrrev_i32_e32 v23, 31, v22
	v_lshlrev_b64 v[22:23], 9, v[22:23]
	v_lshl_add_u64 v[20:21], v[20:21], 0, v[22:23]
	global_store_dwordx4 v[20:21], v[2:5], off
	s_waitcnt lgkmcnt(0)
	s_cbranch_scc0 .LBB0_1496

; #define LAS __attribute__((address_space(3)))
; __device__ __forceinline__ void p0_transpose_item(const float* W, int K, int N, bf16_t* WT, LAS float* scr, int item, int lane) {
;     const int nblk = N / 32, kb = item / nblk, nb = item % nblk, k0 = 64 * kb, n0 = 32 * nb;
;     float tv[32];
; #pragma unroll
;     for (int i = 0; i < 32; ++i) tv[i] = W[(size_t)(k0 + 2 * i + (lane >> 5)) * N + n0 + (lane & 31)];
.LBB0_1499:
	s_ashr_i32 s4, s6, 31
	s_lshr_b32 s4, s4, 28
	s_add_i32 s4, s6, s4
	s_ashr_i32 s4, s4, 4
	s_lshl_b32 s36, s4, 6
	s_lshl_b32 s4, s4, 9
	v_or_b32_e32 v4, s36, v30
	s_sub_i32 s4, s1, s4
	v_or_b32_e32 v22, 2, v4
	s_ashr_i32 s5, s4, 31
	v_ashrrev_i32_e32 v5, 31, v4
	v_ashrrev_i32_e32 v23, 31, v22
	v_lshl_add_u64 v[2:3], s[4:5], 2, v[16:17]
	v_lshlrev_b64 v[20:21], 11, v[4:5]
	v_lshlrev_b64 v[22:23], 11, v[22:23]
	v_lshl_add_u64 v[20:21], v[2:3], 0, v[20:21]
	v_lshl_add_u64 v[22:23], v[2:3], 0, v[22:23]
	global_load_dword v20, v[20:21], off
	v_or_b32_e32 v24, 6, v4
	global_load_dword v21, v[22:23], off
	v_or_b32_e32 v22, 4, v4
	v_ashrrev_i32_e32 v23, 31, v22
	v_ashrrev_i32_e32 v25, 31, v24
	v_lshlrev_b64 v[22:23], 11, v[22:23]
	v_lshlrev_b64 v[24:25], 11, v[24:25]
	v_lshl_add_u64 v[22:23], v[2:3], 0, v[22:23]
	v_lshl_add_u64 v[24:25], v[2:3], 0, v[24:25]
	global_load_dword v22, v[22:23], off
	v_or_b32_e32 v36, 10, v4
	global_load_dword v23, v[24:25], off
	v_or_b32_e32 v24, 8, v4
	v_ashrrev_i32_e32 v25, 31, v24
	v_ashrrev_i32_e32 v37, 31, v36
	v_lshlrev_b64 v[24:25], 11, v[24:25]
	v_lshlrev_b64 v[36:37], 11, v[36:37]
	v_lshl_add_u64 v[24:25], v[2:3], 0, v[24:25]
	v_lshl_add_u64 v[36:37], v[2:3], 0, v[36:37]
	global_load_dword v24, v[24:25], off
	v_or_b32_e32 v38, 14, v4
	global_load_dword v25, v[36:37], off
	v_or_b32_e32 v36, 12, v4
	v_ashrrev_i32_e32 v37, 31, v36
	v_ashrrev_i32_e32 v39, 31, v38
	v_lshlrev_b64 v[36:37], 11, v[36:37]
	v_lshlrev_b64 v[38:39], 11, v[38:39]
	v_lshl_add_u64 v[36:37], v[2:3], 0, v[36:37]
	v_lshl_add_u64 v[38:39], v[2:3], 0, v[38:39]
	global_load_dword v36, v[36:37], off
	v_or_b32_e32 v40, 18, v4
	global_load_dword v37, v[38:39], off
	v_or_b32_e32 v38, 16, v4
	v_ashrrev_i32_e32 v39, 31, v38
	v_ashrrev_i32_e32 v41, 31, v40
	v_lshlrev_b64 v[38:39], 11, v[38:39]
	v_lshlrev_b64 v[40:41], 11, v[40:41]
	v_lshl_add_u64 v[38:39], v[2:3], 0, v[38:39]
	v_lshl_add_u64 v[40:41], v[2:3], 0, v[40:41]
	global_load_dword v38, v[38:39], off
	v_or_b32_e32 v42, 22, v4
	global_load_dword v39, v[40:41], off
	v_or_b32_e32 v40, 20, v4
	v_ashrrev_i32_e32 v41, 31, v40
	v_ashrrev_i32_e32 v43, 31, v42
	v_lshlrev_b64 v[40:41], 11, v[40:41]
	v_lshlrev_b64 v[42:43], 11, v[42:43]
	v_lshl_add_u64 v[40:41], v[2:3], 0, v[40:41]
	v_lshl_add_u64 v[42:43], v[2:3], 0, v[42:43]
	global_load_dword v40, v[40:41], off
	v_or_b32_e32 v44, 26, v4
	global_load_dword v41, v[42:43], off
	v_or_b32_e32 v42, 24, v4
	v_ashrrev_i32_e32 v43, 31, v42
	v_ashrrev_i32_e32 v45, 31, v44
	v_lshlrev_b64 v[42:43], 11, v[42:43]
	v_lshlrev_b64 v[44:45], 11, v[44:45]
	v_lshl_add_u64 v[42:43], v[2:3], 0, v[42:43]
	v_lshl_add_u64 v[44:45], v[2:3], 0, v[44:45]
	global_load_dword v42, v[42:43], off
	v_or_b32_e32 v46, 30, v4
	global_load_dword v43, v[44:45], off
	v_or_b32_e32 v44, 28, v4
	v_ashrrev_i32_e32 v45, 31, v44
	v_ashrrev_i32_e32 v47, 31, v46
	v_lshlrev_b64 v[44:45], 11, v[44:45]
	v_lshlrev_b64 v[46:47], 11, v[46:47]
	v_lshl_add_u64 v[44:45], v[2:3], 0, v[44:45]
	v_lshl_add_u64 v[46:47], v[2:3], 0, v[46:47]
	global_load_dword v44, v[44:45], off
	v_or_b32_e32 v48, 34, v4
	global_load_dword v45, v[46:47], off
	v_or_b32_e32 v46, 32, v4
	v_ashrrev_i32_e32 v47, 31, v46
	v_ashrrev_i32_e32 v49, 31, v48
	v_lshlrev_b64 v[46:47], 11, v[46:47]
	v_lshlrev_b64 v[48:49], 11, v[48:49]
	v_lshl_add_u64 v[46:47], v[2:3], 0, v[46:47]
	v_lshl_add_u64 v[48:49], v[2:3], 0, v[48:49]
	global_load_dword v46, v[46:47], off
	v_or_b32_e32 v50, 38, v4
	global_load_dword v47, v[48:49], off
	v_or_b32_e32 v48, 36, v4
	v_ashrrev_i32_e32 v49, 31, v48
	v_ashrrev_i32_e32 v51, 31, v50
	v_lshlrev_b64 v[48:49], 11, v[48:49]
	v_lshlrev_b64 v[50:51], 11, v[50:51]
	v_lshl_add_u64 v[48:49], v[2:3], 0, v[48:49]
	v_lshl_add_u64 v[50:51], v[2:3], 0, v[50:51]
	global_load_dword v48, v[48:49], off
	v_or_b32_e32 v52, 42, v4
	global_load_dword v49, v[50:51], off
	v_or_b32_e32 v50, 40, v4
	v_ashrrev_i32_e32 v51, 31, v50
	v_ashrrev_i32_e32 v53, 31, v52
	v_lshlrev_b64 v[50:51], 11, v[50:51]
	v_lshlrev_b64 v[52:53], 11, v[52:53]
	v_lshl_add_u64 v[50:51], v[2:3], 0, v[50:51]
	v_lshl_add_u64 v[52:53], v[2:3], 0, v[52:53]
	global_load_dword v50, v[50:51], off
	v_or_b32_e32 v54, 46, v4
	global_load_dword v51, v[52:53], off
	v_or_b32_e32 v52, 44, v4
	v_ashrrev_i32_e32 v53, 31, v52
	v_ashrrev_i32_e32 v55, 31, v54
	v_lshlrev_b64 v[52:53], 11, v[52:53]
	v_lshlrev_b64 v[54:55], 11, v[54:55]
	v_lshl_add_u64 v[52:53], v[2:3], 0, v[52:53]
	v_lshl_add_u64 v[54:55], v[2:3], 0, v[54:55]
	global_load_dword v52, v[52:53], off
	v_or_b32_e32 v56, 50, v4
	global_load_dword v53, v[54:55], off
	v_or_b32_e32 v54, 48, v4
	v_ashrrev_i32_e32 v55, 31, v54
	v_ashrrev_i32_e32 v57, 31, v56
	v_lshlrev_b64 v[54:55], 11, v[54:55]
	v_lshlrev_b64 v[56:57], 11, v[56:57]
	v_lshl_add_u64 v[54:55], v[2:3], 0, v[54:55]
	v_lshl_add_u64 v[56:57], v[2:3], 0, v[56:57]
	global_load_dword v54, v[54:55], off
	v_or_b32_e32 v58, 54, v4
	global_load_dword v55, v[56:57], off
	v_or_b32_e32 v56, 52, v4
	v_ashrrev_i32_e32 v57, 31, v56
	v_ashrrev_i32_e32 v59, 31, v58
	v_lshlrev_b64 v[56:57], 11, v[56:57]
	v_lshlrev_b64 v[58:59], 11, v[58:59]
	v_lshl_add_u64 v[56:57], v[2:3], 0, v[56:57]
	v_lshl_add_u64 v[58:59], v[2:3], 0, v[58:59]
	global_load_dword v56, v[56:57], off
	v_or_b32_e32 v60, 58, v4
	global_load_dword v57, v[58:59], off
	v_or_b32_e32 v58, 56, v4
	v_ashrrev_i32_e32 v59, 31, v58
	v_ashrrev_i32_e32 v61, 31, v60
	v_lshlrev_b64 v[58:59], 11, v[58:59]
	v_lshlrev_b64 v[60:61], 11, v[60:61]
	v_lshl_add_u64 v[58:59], v[2:3], 0, v[58:59]
	v_lshl_add_u64 v[60:61], v[2:3], 0, v[60:61]
	global_load_dword v58, v[58:59], off
	s_ashr_i32 s37, s36, 31
	global_load_dword v59, v[60:61], off
	v_or_b32_e32 v60, 60, v4
	v_or_b32_e32 v4, 62, v4
	v_ashrrev_i32_e32 v61, 31, v60
	v_ashrrev_i32_e32 v5, 31, v4
	v_lshlrev_b64 v[60:61], 11, v[60:61]
	v_lshlrev_b64 v[4:5], 11, v[4:5]
	v_lshl_add_u64 v[60:61], v[2:3], 0, v[60:61]
	v_lshl_add_u64 v[2:3], v[2:3], 0, v[4:5]
	global_load_dword v60, v[60:61], off
	s_add_i32 s6, s6, s3
	global_load_dword v2, v[2:3], off
	s_waitcnt vmcnt(0)
; #define LAS __attribute__((address_space(3)))
; __device__ __forceinline__ unsigned cvt_pk_bf16(float lo, float hi) { unsigned r; asm volatile("v_cvt_pk_bf16_f32 %0, %1, %2" : "=v"(r) : "v"(lo), "v"(hi)); return r; }
; __device__ __forceinline__ void p0_transpose_item(const float* W, int K, int N, bf16_t* WT, LAS float* scr, int item, int lane) {
;     const int nblk = N / 32, kb = item / nblk, nb = item % nblk, k0 = 64 * kb, n0 = 32 * nb;
;     float tv[32];
; #pragma unroll
;     for (int i = 0; i < 32; ++i) tv[i] = W[(size_t)(k0 + 2 * i + (lane >> 5)) * N + n0 + (lane & 31)];
; #pragma unroll
;     for (int i = 0; i < 32; ++i) scr[(2 * i + (lane >> 5)) * 33 + (lane & 31)] = tv[i];
;     asm volatile("s_waitcnt lgkmcnt(0)" ::: "memory");
;     const int c = lane & 7;
; #pragma unroll
;     for (int j = 0; j < 4; ++j) { const int n = (lane >> 3) + 8 * j; const LAS float* s = scr + (8 * c) * 33 + n;
;         u32x4 o; o.x = cvt_pk_bf16(s[0 * 33], s[1 * 33]); o.y = cvt_pk_bf16(s[2 * 33], s[3 * 33]); o.z = cvt_pk_bf16(s[4 * 33], s[5 * 33]); o.w = cvt_pk_bf16(s[6 * 33], s[7 * 33]);
;         *(u32x4*)(WT + (size_t)(n0 + n) * K + k0 + 8 * c) = o; }
;     asm volatile("s_waitcnt lgkmcnt(0)" ::: "memory");
	ds_write2_b32 v0, v20, v21 offset1:66
	ds_write2_b32 v0, v22, v23 offset0:132 offset1:198
	v_add_u32_e32 v22, 0x400, v0
	v_add_u32_e32 v23, 0x800, v0
	ds_write2_b32 v22, v24, v25 offset0:8 offset1:74
	ds_write2_b32 v22, v36, v37 offset0:140 offset1:206
	ds_write2_b32 v23, v38, v39 offset0:16 offset1:82
	ds_write2_b32 v23, v40, v41 offset0:148 offset1:214
	v_add_u32_e32 v24, 0xc00, v0
	v_add_u32_e32 v25, 0x1000, v0
	v_add_u32_e32 v36, 0x1400, v0
	v_add_u32_e32 v37, 0x1800, v0
	v_add_u32_e32 v38, 0x1c00, v0
	ds_write2_b32 v24, v42, v43 offset0:24 offset1:90
	ds_write2_b32 v24, v44, v45 offset0:156 offset1:222
	ds_write2_b32 v25, v46, v47 offset0:32 offset1:98
	ds_write2_b32 v25, v48, v49 offset0:164 offset1:230
	ds_write2_b32 v36, v50, v51 offset0:40 offset1:106
	ds_write2_b32 v36, v52, v53 offset0:172 offset1:238
	ds_write2_b32 v37, v54, v55 offset0:48 offset1:114
	ds_write2_b32 v37, v56, v57 offset0:180 offset1:246
	ds_write2_b32 v38, v58, v59 offset0:56 offset1:122
	ds_write2_b32 v38, v60, v2 offset0:188 offset1:254
	s_waitcnt lgkmcnt(0)
	ds_read2_b32 v[2:3], v32 offset1:33
	s_waitcnt lgkmcnt(0)
	v_cvt_pk_bf16_f32 v2, v2, v3
	ds_read2_b32 v[4:5], v32 offset0:66 offset1:99
	s_waitcnt lgkmcnt(0)
	v_cvt_pk_bf16_f32 v3, v4, v5
	ds_read2_b32 v[4:5], v32 offset0:132 offset1:165
	s_waitcnt lgkmcnt(0)
	v_cvt_pk_bf16_f32 v4, v4, v5
	ds_read2_b32 v[40:41], v32 offset0:198 offset1:231
	s_waitcnt lgkmcnt(0)
	v_cvt_pk_bf16_f32 v5, v40, v41
	v_add_u32_e32 v40, s4, v31
	v_ashrrev_i32_e32 v41, 31, v40
	v_lshl_add_u64 v[20:21], s[36:37], 1, v[18:19]
	v_lshlrev_b64 v[40:41], 8, v[40:41]
	v_lshl_add_u64 v[40:41], v[20:21], 0, v[40:41]
	global_store_dwordx4 v[40:41], v[2:5], off
	ds_read2_b32 v[2:3], v33 offset1:33
	s_add_i32 s1, s1, s23
	s_waitcnt lgkmcnt(0)
	v_cvt_pk_bf16_f32 v2, v2, v3
	ds_read2_b32 v[4:5], v33 offset0:66 offset1:99
	s_waitcnt lgkmcnt(0)
	v_cvt_pk_bf16_f32 v3, v4, v5
	ds_read2_b32 v[4:5], v33 offset0:132 offset1:165
	s_waitcnt lgkmcnt(0)
	v_cvt_pk_bf16_f32 v4, v4, v5
	ds_read2_b32 v[40:41], v33 offset0:198 offset1:231
	s_waitcnt lgkmcnt(0)
	v_cvt_pk_bf16_f32 v5, v40, v41
	v_add_u32_e32 v40, s4, v27
	v_ashrrev_i32_e32 v41, 31, v40
	v_lshlrev_b64 v[40:41], 8, v[40:41]
	v_lshl_add_u64 v[40:41], v[20:21], 0, v[40:41]
	global_store_dwordx4 v[40:41], v[2:5], off
	ds_read2_b32 v[2:3], v34 offset1:33
	s_cmp_gt_i32 s6, 31
	s_waitcnt lgkmcnt(0)
	v_cvt_pk_bf16_f32 v2, v2, v3
	ds_read2_b32 v[4:5], v34 offset0:66 offset1:99
	s_waitcnt lgkmcnt(0)
	v_cvt_pk_bf16_f32 v3, v4, v5
	ds_read2_b32 v[4:5], v34 offset0:132 offset1:165
	s_waitcnt lgkmcnt(0)
	v_cvt_pk_bf16_f32 v4, v4, v5
	ds_read2_b32 v[40:41], v34 offset0:198 offset1:231
	s_waitcnt lgkmcnt(0)
	v_cvt_pk_bf16_f32 v5, v40, v41
	v_add_u32_e32 v40, s4, v28
	v_ashrrev_i32_e32 v41, 31, v40
	v_lshlrev_b64 v[40:41], 8, v[40:41]
	v_lshl_add_u64 v[40:41], v[20:21], 0, v[40:41]
	global_store_dwordx4 v[40:41], v[2:5], off
	ds_read2_b32 v[2:3], v35 offset1:33
	s_waitcnt lgkmcnt(0)
	v_cvt_pk_bf16_f32 v2, v2, v3
	ds_read2_b32 v[4:5], v35 offset0:66 offset1:99
	s_waitcnt lgkmcnt(0)
	v_cvt_pk_bf16_f32 v3, v4, v5
	ds_read2_b32 v[4:5], v35 offset0:132 offset1:165
	s_waitcnt lgkmcnt(0)
	v_cvt_pk_bf16_f32 v4, v4, v5
	ds_read2_b32 v[40:41], v35 offset0:198 offset1:231
	s_waitcnt lgkmcnt(0)
	v_cvt_pk_bf16_f32 v5, v40, v41
	v_add_u32_e32 v40, s4, v29
	v_ashrrev_i32_e32 v41, 31, v40
	v_lshlrev_b64 v[40:41], 8, v[40:41]
	v_lshl_add_u64 v[20:21], v[20:21], 0, v[40:41]
	global_store_dwordx4 v[20:21], v[2:5], off
	s_waitcnt lgkmcnt(0)
	s_cbranch_scc0 .LBB0_1499
	v_readlane_b32 s4, v253, 20
	v_readlane_b32 s5, v253, 21
	s_mov_b32 s1, s21
	s_nop 0
	v_lshl_add_u64 v[16:17], v[8:9], 2, s[4:5]
	s_mov_b64 s[4:5], 0x22c0000
	v_lshl_add_u64 v[18:19], v[14:15], 0, s[4:5]
.LBB0_1501:
	s_ashr_i32 s4, s1, 31
	s_lshr_b32 s4, s4, 29
	s_add_i32 s4, s1, s4
	s_ashr_i32 s4, s4, 3
	s_lshl_b32 s36, s4, 6
	s_lshl_b32 s4, s4, 8
	v_or_b32_e32 v4, s36, v30
	s_sub_i32 s4, s22, s4
	v_or_b32_e32 v40, 2, v4
	s_ashr_i32 s5, s4, 31
	v_ashrrev_i32_e32 v5, 31, v4
	v_ashrrev_i32_e32 v41, 31, v40
	v_lshl_add_u64 v[2:3], s[4:5], 2, v[16:17]
	v_lshlrev_b64 v[20:21], 10, v[4:5]
	v_lshlrev_b64 v[40:41], 10, v[40:41]
	v_lshl_add_u64 v[20:21], v[2:3], 0, v[20:21]
	v_lshl_add_u64 v[40:41], v[2:3], 0, v[40:41]
	global_load_dword v20, v[20:21], off
	v_or_b32_e32 v42, 8, v4
	global_load_dword v21, v[40:41], off
	v_or_b32_e32 v40, 4, v4
	v_ashrrev_i32_e32 v41, 31, v40
	v_lshlrev_b64 v[40:41], 10, v[40:41]
	v_lshl_add_u64 v[40:41], v[2:3], 0, v[40:41]
	global_load_dword v39, v[40:41], off
	v_or_b32_e32 v40, 6, v4
	v_ashrrev_i32_e32 v41, 31, v40
	v_ashrrev_i32_e32 v43, 31, v42
	v_lshlrev_b64 v[40:41], 10, v[40:41]
	v_lshlrev_b64 v[42:43], 10, v[42:43]
	v_lshl_add_u64 v[40:41], v[2:3], 0, v[40:41]
	v_lshl_add_u64 v[42:43], v[2:3], 0, v[42:43]
	global_load_dword v40, v[40:41], off
	v_or_b32_e32 v44, 12, v4
	global_load_dword v41, v[42:43], off
	v_or_b32_e32 v42, 10, v4
	v_ashrrev_i32_e32 v43, 31, v42
	v_ashrrev_i32_e32 v45, 31, v44
	v_lshlrev_b64 v[42:43], 10, v[42:43]
	v_lshlrev_b64 v[44:45], 10, v[44:45]
	v_lshl_add_u64 v[42:43], v[2:3], 0, v[42:43]
	v_lshl_add_u64 v[44:45], v[2:3], 0, v[44:45]
	global_load_dword v42, v[42:43], off
	v_or_b32_e32 v46, 16, v4
	global_load_dword v43, v[44:45], off
	v_or_b32_e32 v44, 14, v4
	v_ashrrev_i32_e32 v45, 31, v44
	v_ashrrev_i32_e32 v47, 31, v46
	v_lshlrev_b64 v[44:45], 10, v[44:45]
	v_lshlrev_b64 v[46:47], 10, v[46:47]
	v_lshl_add_u64 v[44:45], v[2:3], 0, v[44:45]
	v_lshl_add_u64 v[46:47], v[2:3], 0, v[46:47]
	global_load_dword v44, v[44:45], off
	v_or_b32_e32 v48, 20, v4
	global_load_dword v45, v[46:47], off
	v_or_b32_e32 v46, 18, v4
; __device__ __forceinline__ void p0_transpose_item(const float* W, int K, int N, bf16_t* WT, LAS float* scr, int item, int lane) {
;     const int nblk = N / 32, kb = item / nblk, nb = item % nblk, k0 = 64 * kb, n0 = 32 * nb;
;     float tv[32];
; #pragma unroll
;     for (int i = 0; i < 32; ++i) tv[i] = W[(size_t)(k0 + 2 * i + (lane >> 5)) * N + n0 + (lane & 31)];
	v_ashrrev_i32_e32 v47, 31, v46
	v_ashrrev_i32_e32 v49, 31, v48
	v_lshlrev_b64 v[46:47], 10, v[46:47]
	v_lshlrev_b64 v[48:49], 10, v[48:49]
	v_lshl_add_u64 v[46:47], v[2:3], 0, v[46:47]
	v_lshl_add_u64 v[48:49], v[2:3], 0, v[48:49]
	global_load_dword v46, v[46:47], off
	v_or_b32_e32 v50, 24, v4
	global_load_dword v47, v[48:49], off
	v_or_b32_e32 v48, 22, v4
	v_ashrrev_i32_e32 v49, 31, v48
	v_ashrrev_i32_e32 v51, 31, v50
	v_lshlrev_b64 v[48:49], 10, v[48:49]
	v_lshlrev_b64 v[50:51], 10, v[50:51]
	v_lshl_add_u64 v[48:49], v[2:3], 0, v[48:49]
	v_lshl_add_u64 v[50:51], v[2:3], 0, v[50:51]
	global_load_dword v48, v[48:49], off
	v_or_b32_e32 v52, 28, v4
	global_load_dword v49, v[50:51], off
	v_or_b32_e32 v50, 26, v4
	v_ashrrev_i32_e32 v51, 31, v50
	v_ashrrev_i32_e32 v53, 31, v52
	v_lshlrev_b64 v[50:51], 10, v[50:51]
	v_lshlrev_b64 v[52:53], 10, v[52:53]
	v_lshl_add_u64 v[50:51], v[2:3], 0, v[50:51]
	v_lshl_add_u64 v[52:53], v[2:3], 0, v[52:53]
	global_load_dword v50, v[50:51], off
	v_or_b32_e32 v54, 32, v4
	global_load_dword v51, v[52:53], off
	v_or_b32_e32 v52, 30, v4
	v_ashrrev_i32_e32 v53, 31, v52
	v_ashrrev_i32_e32 v55, 31, v54
	v_lshlrev_b64 v[52:53], 10, v[52:53]
	v_lshlrev_b64 v[54:55], 10, v[54:55]
	v_lshl_add_u64 v[52:53], v[2:3], 0, v[52:53]
	v_lshl_add_u64 v[54:55], v[2:3], 0, v[54:55]
	global_load_dword v52, v[52:53], off
	v_or_b32_e32 v56, 36, v4
	global_load_dword v53, v[54:55], off
	v_or_b32_e32 v54, 34, v4
	v_ashrrev_i32_e32 v55, 31, v54
	v_ashrrev_i32_e32 v57, 31, v56
	v_lshlrev_b64 v[54:55], 10, v[54:55]
	v_lshlrev_b64 v[56:57], 10, v[56:57]
	v_lshl_add_u64 v[54:55], v[2:3], 0, v[54:55]
	v_lshl_add_u64 v[56:57], v[2:3], 0, v[56:57]
	global_load_dword v54, v[54:55], off
	v_or_b32_e32 v58, 40, v4
	global_load_dword v55, v[56:57], off
	v_or_b32_e32 v56, 38, v4
	v_ashrrev_i32_e32 v57, 31, v56
	v_ashrrev_i32_e32 v59, 31, v58
	v_lshlrev_b64 v[56:57], 10, v[56:57]
	v_lshlrev_b64 v[58:59], 10, v[58:59]
	v_lshl_add_u64 v[56:57], v[2:3], 0, v[56:57]
	v_lshl_add_u64 v[58:59], v[2:3], 0, v[58:59]
	global_load_dword v56, v[56:57], off
	v_or_b32_e32 v60, 44, v4
	global_load_dword v57, v[58:59], off
	v_or_b32_e32 v58, 42, v4
	v_ashrrev_i32_e32 v59, 31, v58
	v_ashrrev_i32_e32 v61, 31, v60
	v_lshlrev_b64 v[58:59], 10, v[58:59]
	v_lshlrev_b64 v[60:61], 10, v[60:61]
	v_lshl_add_u64 v[58:59], v[2:3], 0, v[58:59]
	v_lshl_add_u64 v[60:61], v[2:3], 0, v[60:61]
	global_load_dword v58, v[58:59], off
	v_or_b32_e32 v62, 48, v4
	global_load_dword v59, v[60:61], off
	v_or_b32_e32 v60, 46, v4
	v_ashrrev_i32_e32 v61, 31, v60
	v_ashrrev_i32_e32 v63, 31, v62
	v_lshlrev_b64 v[60:61], 10, v[60:61]
	v_lshlrev_b64 v[62:63], 10, v[62:63]
	v_lshl_add_u64 v[60:61], v[2:3], 0, v[60:61]
	v_lshl_add_u64 v[62:63], v[2:3], 0, v[62:63]
	global_load_dword v60, v[60:61], off
	v_or_b32_e32 v64, 52, v4
	global_load_dword v61, v[62:63], off
	v_or_b32_e32 v62, 50, v4
	v_ashrrev_i32_e32 v63, 31, v62
	v_ashrrev_i32_e32 v65, 31, v64
	v_lshlrev_b64 v[62:63], 10, v[62:63]
	v_lshlrev_b64 v[64:65], 10, v[64:65]
	v_lshl_add_u64 v[62:63], v[2:3], 0, v[62:63]
	v_lshl_add_u64 v[64:65], v[2:3], 0, v[64:65]
	global_load_dword v62, v[62:63], off
	v_or_b32_e32 v66, 56, v4
	global_load_dword v63, v[64:65], off
	v_or_b32_e32 v64, 54, v4
	v_ashrrev_i32_e32 v65, 31, v64
	v_ashrrev_i32_e32 v67, 31, v66
	v_lshlrev_b64 v[64:65], 10, v[64:65]
	v_lshlrev_b64 v[66:67], 10, v[66:67]
	v_lshl_add_u64 v[64:65], v[2:3], 0, v[64:65]
	v_lshl_add_u64 v[66:67], v[2:3], 0, v[66:67]
	global_load_dword v64, v[64:65], off
	v_or_b32_e32 v68, 60, v4
	global_load_dword v65, v[66:67], off
	v_or_b32_e32 v66, 58, v4
	v_ashrrev_i32_e32 v67, 31, v66
	v_or_b32_e32 v4, 62, v4
	v_lshlrev_b64 v[66:67], 10, v[66:67]
	v_ashrrev_i32_e32 v69, 31, v68
	v_ashrrev_i32_e32 v5, 31, v4
	v_lshl_add_u64 v[66:67], v[2:3], 0, v[66:67]
	v_lshlrev_b64 v[68:69], 10, v[68:69]
	v_lshlrev_b64 v[4:5], 10, v[4:5]
	global_load_dword v66, v[66:67], off
	v_lshl_add_u64 v[68:69], v[2:3], 0, v[68:69]
	v_lshl_add_u64 v[2:3], v[2:3], 0, v[4:5]
	global_load_dword v2, v[2:3], off
	s_ashr_i32 s37, s36, 31
	global_load_dword v67, v[68:69], off
	s_waitcnt vmcnt(0)
; #define LAS __attribute__((address_space(3)))
; __device__ __forceinline__ unsigned cvt_pk_bf16(float lo, float hi) { unsigned r; asm volatile("v_cvt_pk_bf16_f32 %0, %1, %2" : "=v"(r) : "v"(lo), "v"(hi)); return r; }
; __device__ __forceinline__ void p0_transpose_item(const float* W, int K, int N, bf16_t* WT, LAS float* scr, int item, int lane) {
;     ...
;     for (int i = 0; i < 32; ++i) scr[(2 * i + (lane >> 5)) * 33 + (lane & 31)] = tv[i];
;     asm volatile("s_waitcnt lgkmcnt(0)" ::: "memory");
;     const int c = lane & 7;
; #pragma unroll
;     for (int j = 0; j < 4; ++j) { const int n = (lane >> 3) + 8 * j; const LAS float* s = scr + (8 * c) * 33 + n;
;         u32x4 o; o.x = cvt_pk_bf16(s[0 * 33], s[1 * 33]); o.y = cvt_pk_bf16(s[2 * 33], s[3 * 33]); o.z = cvt_pk_bf16(s[4 * 33], s[5 * 33]); o.w = cvt_pk_bf16(s[6 * 33], s[7 * 33]);
;         *(u32x4*)(WT + (size_t)(n0 + n) * K + k0 + 8 * c) = o; }
;     asm volatile("s_waitcnt lgkmcnt(0)" ::: "memory");
	ds_write2_b32 v0, v20, v21 offset1:66
	ds_write2_b32 v0, v39, v40 offset0:132 offset1:198
	ds_write2_b32 v22, v41, v42 offset0:8 offset1:74
	ds_write2_b32 v22, v43, v44 offset0:140 offset1:206
	ds_write2_b32 v23, v45, v46 offset0:16 offset1:82
	ds_write2_b32 v23, v47, v48 offset0:148 offset1:214
	ds_write2_b32 v24, v49, v50 offset0:24 offset1:90
	ds_write2_b32 v24, v51, v52 offset0:156 offset1:222
	ds_write2_b32 v25, v53, v54 offset0:32 offset1:98
	ds_write2_b32 v25, v55, v56 offset0:164 offset1:230
	ds_write2_b32 v36, v57, v58 offset0:40 offset1:106
	ds_write2_b32 v36, v59, v60 offset0:172 offset1:238
	ds_write2_b32 v37, v61, v62 offset0:48 offset1:114
	ds_write2_b32 v37, v63, v64 offset0:180 offset1:246
	ds_write2_b32 v38, v65, v66 offset0:56 offset1:122
	ds_write2_b32 v38, v67, v2 offset0:188 offset1:254
	s_waitcnt lgkmcnt(0)
	ds_read2_b32 v[2:3], v32 offset1:33
	s_waitcnt lgkmcnt(0)
	v_cvt_pk_bf16_f32 v2, v2, v3
	ds_read2_b32 v[4:5], v32 offset0:66 offset1:99
	s_waitcnt lgkmcnt(0)
	v_cvt_pk_bf16_f32 v3, v4, v5
	ds_read2_b32 v[4:5], v32 offset0:132 offset1:165
	s_waitcnt lgkmcnt(0)
	v_cvt_pk_bf16_f32 v4, v4, v5
	ds_read2_b32 v[40:41], v32 offset0:198 offset1:231
	s_waitcnt lgkmcnt(0)
	v_cvt_pk_bf16_f32 v5, v40, v41
	v_add_u32_e32 v40, s4, v31
	v_ashrrev_i32_e32 v41, 31, v40
	v_lshl_add_u64 v[20:21], s[36:37], 1, v[18:19]
	v_lshlrev_b64 v[40:41], 9, v[40:41]
	v_lshl_add_u64 v[40:41], v[20:21], 0, v[40:41]
	global_store_dwordx4 v[40:41], v[2:5], off
	ds_read2_b32 v[2:3], v33 offset1:33
	s_add_i32 s1, s1, s3
	s_waitcnt lgkmcnt(0)
	v_cvt_pk_bf16_f32 v2, v2, v3
	ds_read2_b32 v[4:5], v33 offset0:66 offset1:99
	s_waitcnt lgkmcnt(0)
	v_cvt_pk_bf16_f32 v3, v4, v5
	ds_read2_b32 v[4:5], v33 offset0:132 offset1:165
	s_waitcnt lgkmcnt(0)
	v_cvt_pk_bf16_f32 v4, v4, v5
	ds_read2_b32 v[40:41], v33 offset0:198 offset1:231
	s_waitcnt lgkmcnt(0)
	v_cvt_pk_bf16_f32 v5, v40, v41
	v_add_u32_e32 v40, s4, v27
	v_ashrrev_i32_e32 v41, 31, v40
	v_lshlrev_b64 v[40:41], 9, v[40:41]
	v_lshl_add_u64 v[40:41], v[20:21], 0, v[40:41]
	global_store_dwordx4 v[40:41], v[2:5], off
	ds_read2_b32 v[2:3], v34 offset1:33
	s_add_i32 s22, s22, s23
	s_waitcnt lgkmcnt(0)
	v_cvt_pk_bf16_f32 v2, v2, v3
	ds_read2_b32 v[4:5], v34 offset0:66 offset1:99
	s_waitcnt lgkmcnt(0)
	v_cvt_pk_bf16_f32 v3, v4, v5
	ds_read2_b32 v[4:5], v34 offset0:132 offset1:165
	s_waitcnt lgkmcnt(0)
	v_cvt_pk_bf16_f32 v4, v4, v5
	ds_read2_b32 v[40:41], v34 offset0:198 offset1:231
	s_waitcnt lgkmcnt(0)
	v_cvt_pk_bf16_f32 v5, v40, v41
	v_add_u32_e32 v40, s4, v28
	v_ashrrev_i32_e32 v41, 31, v40
	v_lshlrev_b64 v[40:41], 9, v[40:41]
	v_lshl_add_u64 v[40:41], v[20:21], 0, v[40:41]
	global_store_dwordx4 v[40:41], v[2:5], off
	ds_read2_b32 v[2:3], v35 offset1:33
	s_cmp_gt_i32 s1, 31
	s_waitcnt lgkmcnt(0)
	v_cvt_pk_bf16_f32 v2, v2, v3
	ds_read2_b32 v[4:5], v35 offset0:66 offset1:99
	s_waitcnt lgkmcnt(0)
	v_cvt_pk_bf16_f32 v3, v4, v5
	ds_read2_b32 v[4:5], v35 offset0:132 offset1:165
	s_waitcnt lgkmcnt(0)
	v_cvt_pk_bf16_f32 v4, v4, v5
	ds_read2_b32 v[40:41], v35 offset0:198 offset1:231
	s_waitcnt lgkmcnt(0)
	v_cvt_pk_bf16_f32 v5, v40, v41
	v_add_u32_e32 v40, s4, v29
	v_ashrrev_i32_e32 v41, 31, v40
	v_lshlrev_b64 v[40:41], 9, v[40:41]
	v_lshl_add_u64 v[20:21], v[20:21], 0, v[40:41]
	global_store_dwordx4 v[20:21], v[2:5], off
	s_waitcnt lgkmcnt(0)
	s_cbranch_scc0 .LBB0_1501

; __device__ __forceinline__ void p0_transpose_item(const float* W, int K, int N, bf16_t* WT, LAS float* scr, int item, int lane) {
;     const int nblk = N / 32, kb = item / nblk, nb = item % nblk, k0 = 64 * kb, n0 = 32 * nb;
;     float tv[32];
; #pragma unroll
;     for (int i = 0; i < 32; ++i) tv[i] = W[(size_t)(k0 + 2 * i + (lane >> 5)) * N + n0 + (lane & 31)];
.LBB0_1506:
	s_lshr_b32 s14, s19, 31
	s_add_i32 s14, s19, s14
	s_lshl_b32 s14, s14, 5
	s_and_b32 s44, s14, 0xffffffc0
	v_or_b32_e32 v4, s44, v30
	s_sub_i32 s42, s18, s44
	v_or_b32_e32 v22, 2, v4
	s_ashr_i32 s43, s42, 31
	v_ashrrev_i32_e32 v5, 31, v4
	v_ashrrev_i32_e32 v23, 31, v22
	v_lshl_add_u64 v[2:3], s[42:43], 2, v[16:17]
	v_lshlrev_b64 v[20:21], 8, v[4:5]
	v_lshlrev_b64 v[22:23], 8, v[22:23]
	v_lshl_add_u64 v[20:21], v[2:3], 0, v[20:21]
	v_lshl_add_u64 v[22:23], v[2:3], 0, v[22:23]
	global_load_dword v20, v[20:21], off
	v_or_b32_e32 v24, 6, v4
	global_load_dword v21, v[22:23], off
	v_or_b32_e32 v22, 4, v4
	v_ashrrev_i32_e32 v23, 31, v22
	v_ashrrev_i32_e32 v25, 31, v24
	v_lshlrev_b64 v[22:23], 8, v[22:23]
	v_lshlrev_b64 v[24:25], 8, v[24:25]
	v_lshl_add_u64 v[22:23], v[2:3], 0, v[22:23]
	v_lshl_add_u64 v[24:25], v[2:3], 0, v[24:25]
	global_load_dword v22, v[22:23], off
	v_or_b32_e32 v36, 10, v4
	global_load_dword v23, v[24:25], off
	v_or_b32_e32 v24, 8, v4
	v_ashrrev_i32_e32 v25, 31, v24
	v_ashrrev_i32_e32 v37, 31, v36
	v_lshlrev_b64 v[24:25], 8, v[24:25]
	v_lshlrev_b64 v[36:37], 8, v[36:37]
	v_lshl_add_u64 v[24:25], v[2:3], 0, v[24:25]
	v_lshl_add_u64 v[36:37], v[2:3], 0, v[36:37]
	global_load_dword v24, v[24:25], off
	v_or_b32_e32 v38, 14, v4
	global_load_dword v25, v[36:37], off
	v_or_b32_e32 v36, 12, v4
	v_ashrrev_i32_e32 v37, 31, v36
	v_ashrrev_i32_e32 v39, 31, v38
	v_lshlrev_b64 v[36:37], 8, v[36:37]
	v_lshlrev_b64 v[38:39], 8, v[38:39]
	v_lshl_add_u64 v[36:37], v[2:3], 0, v[36:37]
	v_lshl_add_u64 v[38:39], v[2:3], 0, v[38:39]
	global_load_dword v36, v[36:37], off
	v_or_b32_e32 v40, 18, v4
	global_load_dword v37, v[38:39], off
	v_or_b32_e32 v38, 16, v4
	v_ashrrev_i32_e32 v39, 31, v38
	v_ashrrev_i32_e32 v41, 31, v40
	v_lshlrev_b64 v[38:39], 8, v[38:39]
	v_lshlrev_b64 v[40:41], 8, v[40:41]
	v_lshl_add_u64 v[38:39], v[2:3], 0, v[38:39]
	v_lshl_add_u64 v[40:41], v[2:3], 0, v[40:41]
	global_load_dword v38, v[38:39], off
	v_or_b32_e32 v42, 22, v4
	global_load_dword v39, v[40:41], off
	v_or_b32_e32 v40, 20, v4
	v_ashrrev_i32_e32 v41, 31, v40
	v_ashrrev_i32_e32 v43, 31, v42
	v_lshlrev_b64 v[40:41], 8, v[40:41]
	v_lshlrev_b64 v[42:43], 8, v[42:43]
	v_lshl_add_u64 v[40:41], v[2:3], 0, v[40:41]
	v_lshl_add_u64 v[42:43], v[2:3], 0, v[42:43]
	global_load_dword v40, v[40:41], off
	v_or_b32_e32 v44, 26, v4
	global_load_dword v41, v[42:43], off
	v_or_b32_e32 v42, 24, v4
	v_ashrrev_i32_e32 v43, 31, v42
	v_ashrrev_i32_e32 v45, 31, v44
	v_lshlrev_b64 v[42:43], 8, v[42:43]
	v_lshlrev_b64 v[44:45], 8, v[44:45]
	v_lshl_add_u64 v[42:43], v[2:3], 0, v[42:43]
	v_lshl_add_u64 v[44:45], v[2:3], 0, v[44:45]
	global_load_dword v42, v[42:43], off
	v_or_b32_e32 v46, 30, v4
	global_load_dword v43, v[44:45], off
	v_or_b32_e32 v44, 28, v4
	v_ashrrev_i32_e32 v45, 31, v44
	v_ashrrev_i32_e32 v47, 31, v46
	v_lshlrev_b64 v[44:45], 8, v[44:45]
	v_lshlrev_b64 v[46:47], 8, v[46:47]
	v_lshl_add_u64 v[44:45], v[2:3], 0, v[44:45]
	v_lshl_add_u64 v[46:47], v[2:3], 0, v[46:47]
	global_load_dword v44, v[44:45], off
	v_or_b32_e32 v48, 34, v4
	global_load_dword v45, v[46:47], off
	v_or_b32_e32 v46, 32, v4
	v_ashrrev_i32_e32 v47, 31, v46
	v_ashrrev_i32_e32 v49, 31, v48
	v_lshlrev_b64 v[46:47], 8, v[46:47]
	v_lshlrev_b64 v[48:49], 8, v[48:49]
	v_lshl_add_u64 v[46:47], v[2:3], 0, v[46:47]
	v_lshl_add_u64 v[48:49], v[2:3], 0, v[48:49]
	global_load_dword v46, v[46:47], off
	v_or_b32_e32 v50, 38, v4
	global_load_dword v47, v[48:49], off
	v_or_b32_e32 v48, 36, v4
	v_ashrrev_i32_e32 v49, 31, v48
	v_ashrrev_i32_e32 v51, 31, v50
	v_lshlrev_b64 v[48:49], 8, v[48:49]
	v_lshlrev_b64 v[50:51], 8, v[50:51]
	v_lshl_add_u64 v[48:49], v[2:3], 0, v[48:49]
	v_lshl_add_u64 v[50:51], v[2:3], 0, v[50:51]
	global_load_dword v48, v[48:49], off
	v_or_b32_e32 v52, 42, v4
	global_load_dword v49, v[50:51], off
	v_or_b32_e32 v50, 40, v4
	v_ashrrev_i32_e32 v51, 31, v50
	v_ashrrev_i32_e32 v53, 31, v52
	v_lshlrev_b64 v[50:51], 8, v[50:51]
	v_lshlrev_b64 v[52:53], 8, v[52:53]
	v_lshl_add_u64 v[50:51], v[2:3], 0, v[50:51]
	v_lshl_add_u64 v[52:53], v[2:3], 0, v[52:53]
	global_load_dword v50, v[50:51], off
	v_or_b32_e32 v54, 46, v4
	global_load_dword v51, v[52:53], off
	v_or_b32_e32 v52, 44, v4
	v_ashrrev_i32_e32 v53, 31, v52
	v_ashrrev_i32_e32 v55, 31, v54
	v_lshlrev_b64 v[52:53], 8, v[52:53]
	v_lshlrev_b64 v[54:55], 8, v[54:55]
	v_lshl_add_u64 v[52:53], v[2:3], 0, v[52:53]
	v_lshl_add_u64 v[54:55], v[2:3], 0, v[54:55]
	global_load_dword v52, v[52:53], off
	v_or_b32_e32 v56, 50, v4
	global_load_dword v53, v[54:55], off
	v_or_b32_e32 v54, 48, v4
	v_ashrrev_i32_e32 v55, 31, v54
	v_ashrrev_i32_e32 v57, 31, v56
	v_lshlrev_b64 v[54:55], 8, v[54:55]
	v_lshlrev_b64 v[56:57], 8, v[56:57]
	v_lshl_add_u64 v[54:55], v[2:3], 0, v[54:55]
	v_lshl_add_u64 v[56:57], v[2:3], 0, v[56:57]
	global_load_dword v54, v[54:55], off
	v_or_b32_e32 v58, 54, v4
	global_load_dword v55, v[56:57], off
	v_or_b32_e32 v56, 52, v4
	v_ashrrev_i32_e32 v57, 31, v56
	v_ashrrev_i32_e32 v59, 31, v58
	v_lshlrev_b64 v[56:57], 8, v[56:57]
	v_lshlrev_b64 v[58:59], 8, v[58:59]
	v_lshl_add_u64 v[56:57], v[2:3], 0, v[56:57]
	v_lshl_add_u64 v[58:59], v[2:3], 0, v[58:59]
	global_load_dword v56, v[56:57], off
	v_or_b32_e32 v60, 58, v4
	global_load_dword v57, v[58:59], off
	v_or_b32_e32 v58, 56, v4
	v_ashrrev_i32_e32 v59, 31, v58
	v_ashrrev_i32_e32 v61, 31, v60
	v_lshlrev_b64 v[58:59], 8, v[58:59]
	v_lshlrev_b64 v[60:61], 8, v[60:61]
	v_lshl_add_u64 v[58:59], v[2:3], 0, v[58:59]
	v_lshl_add_u64 v[60:61], v[2:3], 0, v[60:61]
	global_load_dword v58, v[58:59], off
	s_ashr_i32 s45, s44, 31
	global_load_dword v59, v[60:61], off
	v_or_b32_e32 v60, 60, v4
	v_or_b32_e32 v4, 62, v4
	v_ashrrev_i32_e32 v61, 31, v60
	v_ashrrev_i32_e32 v5, 31, v4
	v_lshlrev_b64 v[60:61], 8, v[60:61]
	v_lshlrev_b64 v[4:5], 8, v[4:5]
	v_lshl_add_u64 v[60:61], v[2:3], 0, v[60:61]
	v_lshl_add_u64 v[2:3], v[2:3], 0, v[4:5]
	global_load_dword v60, v[60:61], off
	s_add_i32 s19, s19, s3
	global_load_dword v2, v[2:3], off
	s_waitcnt vmcnt(0)
; #define LAS __attribute__((address_space(3)))
; __device__ __forceinline__ unsigned cvt_pk_bf16(float lo, float hi) { unsigned r; asm volatile("v_cvt_pk_bf16_f32 %0, %1, %2" : "=v"(r) : "v"(lo), "v"(hi)); return r; }
; __device__ __forceinline__ void p0_transpose_item(const float* W, int K, int N, bf16_t* WT, LAS float* scr, int item, int lane) {
;     ...
;     for (int i = 0; i < 32; ++i) scr[(2 * i + (lane >> 5)) * 33 + (lane & 31)] = tv[i];
;     asm volatile("s_waitcnt lgkmcnt(0)" ::: "memory");
;     const int c = lane & 7;
; #pragma unroll
;     for (int j = 0; j < 4; ++j) { const int n = (lane >> 3) + 8 * j; const LAS float* s = scr + (8 * c) * 33 + n;
;         u32x4 o; o.x = cvt_pk_bf16(s[0 * 33], s[1 * 33]); o.y = cvt_pk_bf16(s[2 * 33], s[3 * 33]); o.z = cvt_pk_bf16(s[4 * 33], s[5 * 33]); o.w = cvt_pk_bf16(s[6 * 33], s[7 * 33]);
;         *(u32x4*)(WT + (size_t)(n0 + n) * K + k0 + 8 * c) = o; }
;     asm volatile("s_waitcnt lgkmcnt(0)" ::: "memory");
	ds_write2_b32 v0, v20, v21 offset1:66
	ds_write2_b32 v0, v22, v23 offset0:132 offset1:198
	v_add_u32_e32 v22, 0x400, v0
	v_add_u32_e32 v23, 0x800, v0
	ds_write2_b32 v22, v24, v25 offset0:8 offset1:74
	ds_write2_b32 v22, v36, v37 offset0:140 offset1:206
	ds_write2_b32 v23, v38, v39 offset0:16 offset1:82
	ds_write2_b32 v23, v40, v41 offset0:148 offset1:214
	v_add_u32_e32 v24, 0xc00, v0
	v_add_u32_e32 v25, 0x1000, v0
	v_add_u32_e32 v36, 0x1400, v0
	v_add_u32_e32 v37, 0x1800, v0
	v_add_u32_e32 v38, 0x1c00, v0
	ds_write2_b32 v24, v42, v43 offset0:24 offset1:90
	ds_write2_b32 v24, v44, v45 offset0:156 offset1:222
	ds_write2_b32 v25, v46, v47 offset0:32 offset1:98
	ds_write2_b32 v25, v48, v49 offset0:164 offset1:230
	ds_write2_b32 v36, v50, v51 offset0:40 offset1:106
	ds_write2_b32 v36, v52, v53 offset0:172 offset1:238
	ds_write2_b32 v37, v54, v55 offset0:48 offset1:114
	ds_write2_b32 v37, v56, v57 offset0:180 offset1:246
	ds_write2_b32 v38, v58, v59 offset0:56 offset1:122
	ds_write2_b32 v38, v60, v2 offset0:188 offset1:254
	s_waitcnt lgkmcnt(0)
	ds_read2_b32 v[2:3], v32 offset1:33
	s_waitcnt lgkmcnt(0)
	v_cvt_pk_bf16_f32 v2, v2, v3
	ds_read2_b32 v[4:5], v32 offset0:66 offset1:99
	s_waitcnt lgkmcnt(0)
	v_cvt_pk_bf16_f32 v3, v4, v5
	ds_read2_b32 v[4:5], v32 offset0:132 offset1:165
	s_waitcnt lgkmcnt(0)
	v_cvt_pk_bf16_f32 v4, v4, v5
	ds_read2_b32 v[40:41], v32 offset0:198 offset1:231
	s_waitcnt lgkmcnt(0)
	v_cvt_pk_bf16_f32 v5, v40, v41
	v_add_u32_e32 v40, s42, v31
	v_ashrrev_i32_e32 v41, 31, v40
	v_lshl_add_u64 v[20:21], s[44:45], 1, v[18:19]
	v_lshlrev_b64 v[40:41], 7, v[40:41]
	v_lshl_add_u64 v[40:41], v[20:21], 0, v[40:41]
	global_store_dwordx4 v[40:41], v[2:5], off
	ds_read2_b32 v[2:3], v33 offset1:33
	s_add_i32 s18, s18, s24
	s_waitcnt lgkmcnt(0)
	v_cvt_pk_bf16_f32 v2, v2, v3
	ds_read2_b32 v[4:5], v33 offset0:66 offset1:99
	s_waitcnt lgkmcnt(0)
	v_cvt_pk_bf16_f32 v3, v4, v5
	ds_read2_b32 v[4:5], v33 offset0:132 offset1:165
	s_waitcnt lgkmcnt(0)
	v_cvt_pk_bf16_f32 v4, v4, v5
	ds_read2_b32 v[40:41], v33 offset0:198 offset1:231
	s_waitcnt lgkmcnt(0)
	v_cvt_pk_bf16_f32 v5, v40, v41
	v_add_u32_e32 v40, s42, v27
	v_ashrrev_i32_e32 v41, 31, v40
	v_lshlrev_b64 v[40:41], 7, v[40:41]
	v_lshl_add_u64 v[40:41], v[20:21], 0, v[40:41]
	global_store_dwordx4 v[40:41], v[2:5], off
	ds_read2_b32 v[2:3], v34 offset1:33
	s_cmp_gt_i32 s19, 1
	s_waitcnt lgkmcnt(0)
	v_cvt_pk_bf16_f32 v2, v2, v3
	ds_read2_b32 v[4:5], v34 offset0:66 offset1:99
	s_waitcnt lgkmcnt(0)
	v_cvt_pk_bf16_f32 v3, v4, v5
	ds_read2_b32 v[4:5], v34 offset0:132 offset1:165
	s_waitcnt lgkmcnt(0)
	v_cvt_pk_bf16_f32 v4, v4, v5
	ds_read2_b32 v[40:41], v34 offset0:198 offset1:231
	s_waitcnt lgkmcnt(0)
	v_cvt_pk_bf16_f32 v5, v40, v41
	v_add_u32_e32 v40, s42, v28
	v_ashrrev_i32_e32 v41, 31, v40
	v_lshlrev_b64 v[40:41], 7, v[40:41]
	v_lshl_add_u64 v[40:41], v[20:21], 0, v[40:41]
	global_store_dwordx4 v[40:41], v[2:5], off
	ds_read2_b32 v[2:3], v35 offset1:33
	s_waitcnt lgkmcnt(0)
	v_cvt_pk_bf16_f32 v2, v2, v3
	ds_read2_b32 v[4:5], v35 offset0:66 offset1:99
	s_waitcnt lgkmcnt(0)
	v_cvt_pk_bf16_f32 v3, v4, v5
	ds_read2_b32 v[4:5], v35 offset0:132 offset1:165
	s_waitcnt lgkmcnt(0)
	v_cvt_pk_bf16_f32 v4, v4, v5
	ds_read2_b32 v[40:41], v35 offset0:198 offset1:231
	s_waitcnt lgkmcnt(0)
	v_cvt_pk_bf16_f32 v5, v40, v41
	v_add_u32_e32 v40, s42, v29
	v_ashrrev_i32_e32 v41, 31, v40
	v_lshlrev_b64 v[40:41], 7, v[40:41]
	v_lshl_add_u64 v[20:21], v[20:21], 0, v[40:41]
	global_store_dwordx4 v[20:21], v[2:5], off
	s_waitcnt lgkmcnt(0)
	s_cbranch_scc0 .LBB0_1506
	v_readlane_b32 s44, v251, 40
	v_readlane_b32 s52, v251, 48
	v_readlane_b32 s53, v251, 49
	s_add_u32 s4, s52, s4
	s_addc_u32 s5, s53, s5
	s_lshl_b32 s7, s7, 1
	s_add_u32 s14, s1, s7
	s_addc_u32 s15, s6, 0
	v_lshl_add_u64 v[2:3], v[8:9], 2, s[4:5]
	v_lshl_add_u64 v[16:17], v[2:3], 0, s[16:17]
	v_lshl_add_u64 v[2:3], v[6:7], 1, s[14:15]
	s_mov_b64 s[4:5], 0x2308000
	v_lshl_add_u64 v[18:19], v[2:3], 0, s[4:5]
	s_mov_b32 s1, s21
	v_readlane_b32 s45, v251, 41
	v_readlane_b32 s46, v251, 42
	v_readlane_b32 s47, v251, 43
	v_readlane_b32 s48, v251, 44
	v_readlane_b32 s49, v251, 45
	v_readlane_b32 s50, v251, 46
	v_readlane_b32 s51, v251, 47
	v_readlane_b32 s54, v251, 50
	v_readlane_b32 s55, v251, 51
	v_readlane_b32 s56, v251, 52
	v_readlane_b32 s57, v251, 53
	v_readlane_b32 s58, v251, 54
	v_readlane_b32 s59, v251, 55
; __device__ __forceinline__ void p0_transpose_item(const float* W, int K, int N, bf16_t* WT, LAS float* scr, int item, int lane) {
;     const int nblk = N / 32, kb = item / nblk, nb = item % nblk, k0 = 64 * kb, n0 = 32 * nb;
;     float tv[32];
; #pragma unroll
;     for (int i = 0; i < 32; ++i) tv[i] = W[(size_t)(k0 + 2 * i + (lane >> 5)) * N + n0 + (lane & 31)];
.LBB0_1508:
	s_lshr_b32 s4, s1, 31
	s_add_i32 s4, s1, s4
	s_lshl_b32 s4, s4, 5
	s_and_b32 s42, s4, 0xffffffc0
	v_or_b32_e32 v4, s42, v30
	s_sub_i32 s4, s23, s42
	v_or_b32_e32 v40, 2, v4
	s_ashr_i32 s5, s4, 31
	v_ashrrev_i32_e32 v5, 31, v4
	v_ashrrev_i32_e32 v41, 31, v40
	v_lshl_add_u64 v[2:3], s[4:5], 2, v[16:17]
	v_lshlrev_b64 v[20:21], 8, v[4:5]
	v_lshlrev_b64 v[40:41], 8, v[40:41]
	v_lshl_add_u64 v[20:21], v[2:3], 0, v[20:21]
	v_lshl_add_u64 v[40:41], v[2:3], 0, v[40:41]
	global_load_dword v20, v[20:21], off
	v_or_b32_e32 v42, 8, v4
	global_load_dword v21, v[40:41], off
	v_or_b32_e32 v40, 4, v4
	v_ashrrev_i32_e32 v41, 31, v40
	v_lshlrev_b64 v[40:41], 8, v[40:41]
	v_lshl_add_u64 v[40:41], v[2:3], 0, v[40:41]
	global_load_dword v39, v[40:41], off
	v_or_b32_e32 v40, 6, v4
	v_ashrrev_i32_e32 v41, 31, v40
	v_ashrrev_i32_e32 v43, 31, v42
	v_lshlrev_b64 v[40:41], 8, v[40:41]
	v_lshlrev_b64 v[42:43], 8, v[42:43]
	v_lshl_add_u64 v[40:41], v[2:3], 0, v[40:41]
	v_lshl_add_u64 v[42:43], v[2:3], 0, v[42:43]
	global_load_dword v40, v[40:41], off
	v_or_b32_e32 v44, 12, v4
	global_load_dword v41, v[42:43], off
	v_or_b32_e32 v42, 10, v4
	v_ashrrev_i32_e32 v43, 31, v42
	v_ashrrev_i32_e32 v45, 31, v44
	v_lshlrev_b64 v[42:43], 8, v[42:43]
	v_lshlrev_b64 v[44:45], 8, v[44:45]
	v_lshl_add_u64 v[42:43], v[2:3], 0, v[42:43]
	v_lshl_add_u64 v[44:45], v[2:3], 0, v[44:45]
	global_load_dword v42, v[42:43], off
	v_or_b32_e32 v46, 16, v4
	global_load_dword v43, v[44:45], off
	v_or_b32_e32 v44, 14, v4
	v_ashrrev_i32_e32 v45, 31, v44
	v_ashrrev_i32_e32 v47, 31, v46
	v_lshlrev_b64 v[44:45], 8, v[44:45]
	v_lshlrev_b64 v[46:47], 8, v[46:47]
	v_lshl_add_u64 v[44:45], v[2:3], 0, v[44:45]
	v_lshl_add_u64 v[46:47], v[2:3], 0, v[46:47]
	global_load_dword v44, v[44:45], off
	v_or_b32_e32 v48, 20, v4
	global_load_dword v45, v[46:47], off
	v_or_b32_e32 v46, 18, v4
	v_ashrrev_i32_e32 v47, 31, v46
	v_ashrrev_i32_e32 v49, 31, v48
	v_lshlrev_b64 v[46:47], 8, v[46:47]
	v_lshlrev_b64 v[48:49], 8, v[48:49]
	v_lshl_add_u64 v[46:47], v[2:3], 0, v[46:47]
	v_lshl_add_u64 v[48:49], v[2:3], 0, v[48:49]
	global_load_dword v46, v[46:47], off
	v_or_b32_e32 v50, 24, v4
	global_load_dword v47, v[48:49], off
	v_or_b32_e32 v48, 22, v4
	v_ashrrev_i32_e32 v49, 31, v48
	v_ashrrev_i32_e32 v51, 31, v50
	v_lshlrev_b64 v[48:49], 8, v[48:49]
	v_lshlrev_b64 v[50:51], 8, v[50:51]
	v_lshl_add_u64 v[48:49], v[2:3], 0, v[48:49]
	v_lshl_add_u64 v[50:51], v[2:3], 0, v[50:51]
	global_load_dword v48, v[48:49], off
	v_or_b32_e32 v52, 28, v4
	global_load_dword v49, v[50:51], off
	v_or_b32_e32 v50, 26, v4
	v_ashrrev_i32_e32 v51, 31, v50
	v_ashrrev_i32_e32 v53, 31, v52
	v_lshlrev_b64 v[50:51], 8, v[50:51]
	v_lshlrev_b64 v[52:53], 8, v[52:53]
	v_lshl_add_u64 v[50:51], v[2:3], 0, v[50:51]
	v_lshl_add_u64 v[52:53], v[2:3], 0, v[52:53]
	global_load_dword v50, v[50:51], off
	v_or_b32_e32 v54, 32, v4
	global_load_dword v51, v[52:53], off
	v_or_b32_e32 v52, 30, v4
	v_ashrrev_i32_e32 v53, 31, v52
	v_ashrrev_i32_e32 v55, 31, v54
	v_lshlrev_b64 v[52:53], 8, v[52:53]
	v_lshlrev_b64 v[54:55], 8, v[54:55]
	v_lshl_add_u64 v[52:53], v[2:3], 0, v[52:53]
	v_lshl_add_u64 v[54:55], v[2:3], 0, v[54:55]
	global_load_dword v52, v[52:53], off
	v_or_b32_e32 v56, 36, v4
	global_load_dword v53, v[54:55], off
	v_or_b32_e32 v54, 34, v4
	v_ashrrev_i32_e32 v55, 31, v54
	v_ashrrev_i32_e32 v57, 31, v56
	v_lshlrev_b64 v[54:55], 8, v[54:55]
	v_lshlrev_b64 v[56:57], 8, v[56:57]
	v_lshl_add_u64 v[54:55], v[2:3], 0, v[54:55]
	v_lshl_add_u64 v[56:57], v[2:3], 0, v[56:57]
	global_load_dword v54, v[54:55], off
	v_or_b32_e32 v58, 40, v4
	global_load_dword v55, v[56:57], off
	v_or_b32_e32 v56, 38, v4
	v_ashrrev_i32_e32 v57, 31, v56
	v_ashrrev_i32_e32 v59, 31, v58
	v_lshlrev_b64 v[56:57], 8, v[56:57]
	v_lshlrev_b64 v[58:59], 8, v[58:59]
	v_lshl_add_u64 v[56:57], v[2:3], 0, v[56:57]
	v_lshl_add_u64 v[58:59], v[2:3], 0, v[58:59]
	global_load_dword v56, v[56:57], off
	v_or_b32_e32 v60, 44, v4
	global_load_dword v57, v[58:59], off
	v_or_b32_e32 v58, 42, v4
	v_ashrrev_i32_e32 v59, 31, v58
	v_ashrrev_i32_e32 v61, 31, v60
	v_lshlrev_b64 v[58:59], 8, v[58:59]
	v_lshlrev_b64 v[60:61], 8, v[60:61]
	v_lshl_add_u64 v[58:59], v[2:3], 0, v[58:59]
	v_lshl_add_u64 v[60:61], v[2:3], 0, v[60:61]
	global_load_dword v58, v[58:59], off
	v_or_b32_e32 v62, 48, v4
	global_load_dword v59, v[60:61], off
	v_or_b32_e32 v60, 46, v4
	v_ashrrev_i32_e32 v61, 31, v60
	v_ashrrev_i32_e32 v63, 31, v62
	v_lshlrev_b64 v[60:61], 8, v[60:61]
	v_lshlrev_b64 v[62:63], 8, v[62:63]
	v_lshl_add_u64 v[60:61], v[2:3], 0, v[60:61]
	v_lshl_add_u64 v[62:63], v[2:3], 0, v[62:63]
	global_load_dword v60, v[60:61], off
	v_or_b32_e32 v64, 52, v4
	global_load_dword v61, v[62:63], off
	v_or_b32_e32 v62, 50, v4
	v_ashrrev_i32_e32 v63, 31, v62
	v_ashrrev_i32_e32 v65, 31, v64
	v_lshlrev_b64 v[62:63], 8, v[62:63]
	v_lshlrev_b64 v[64:65], 8, v[64:65]
	v_lshl_add_u64 v[62:63], v[2:3], 0, v[62:63]
	v_lshl_add_u64 v[64:65], v[2:3], 0, v[64:65]
	global_load_dword v62, v[62:63], off
	v_or_b32_e32 v66, 56, v4
	global_load_dword v63, v[64:65], off
	v_or_b32_e32 v64, 54, v4
	v_ashrrev_i32_e32 v65, 31, v64
	v_ashrrev_i32_e32 v67, 31, v66
	v_lshlrev_b64 v[64:65], 8, v[64:65]
	v_lshlrev_b64 v[66:67], 8, v[66:67]
	v_lshl_add_u64 v[64:65], v[2:3], 0, v[64:65]
	v_lshl_add_u64 v[66:67], v[2:3], 0, v[66:67]
	global_load_dword v64, v[64:65], off
	v_or_b32_e32 v68, 60, v4
	global_load_dword v65, v[66:67], off
	v_or_b32_e32 v66, 58, v4
	v_ashrrev_i32_e32 v67, 31, v66
	v_or_b32_e32 v4, 62, v4
	v_lshlrev_b64 v[66:67], 8, v[66:67]
	v_ashrrev_i32_e32 v69, 31, v68
	v_ashrrev_i32_e32 v5, 31, v4
	v_lshl_add_u64 v[66:67], v[2:3], 0, v[66:67]
	v_lshlrev_b64 v[68:69], 8, v[68:69]
	v_lshlrev_b64 v[4:5], 8, v[4:5]
	global_load_dword v66, v[66:67], off
	v_lshl_add_u64 v[68:69], v[2:3], 0, v[68:69]
	v_lshl_add_u64 v[2:3], v[2:3], 0, v[4:5]
	global_load_dword v2, v[2:3], off
	s_ashr_i32 s43, s42, 31
	global_load_dword v67, v[68:69], off
	s_waitcnt vmcnt(0)
; #define LAS __attribute__((address_space(3)))
; __device__ __forceinline__ unsigned cvt_pk_bf16(float lo, float hi) { unsigned r; asm volatile("v_cvt_pk_bf16_f32 %0, %1, %2" : "=v"(r) : "v"(lo), "v"(hi)); return r; }
; __device__ __forceinline__ void p0_transpose_item(const float* W, int K, int N, bf16_t* WT, LAS float* scr, int item, int lane) {
;     ...
;     for (int i = 0; i < 32; ++i) scr[(2 * i + (lane >> 5)) * 33 + (lane & 31)] = tv[i];
;     asm volatile("s_waitcnt lgkmcnt(0)" ::: "memory");
;     const int c = lane & 7;
; #pragma unroll
;     for (int j = 0; j < 4; ++j) { const int n = (lane >> 3) + 8 * j; const LAS float* s = scr + (8 * c) * 33 + n;
;         u32x4 o; o.x = cvt_pk_bf16(s[0 * 33], s[1 * 33]); o.y = cvt_pk_bf16(s[2 * 33], s[3 * 33]); o.z = cvt_pk_bf16(s[4 * 33], s[5 * 33]); o.w = cvt_pk_bf16(s[6 * 33], s[7 * 33]);
;         *(u32x4*)(WT + (size_t)(n0 + n) * K + k0 + 8 * c) = o; }
;     asm volatile("s_waitcnt lgkmcnt(0)" ::: "memory");
	ds_write2_b32 v0, v20, v21 offset1:66
	ds_write2_b32 v0, v39, v40 offset0:132 offset1:198
	ds_write2_b32 v22, v41, v42 offset0:8 offset1:74
	ds_write2_b32 v22, v43, v44 offset0:140 offset1:206
	ds_write2_b32 v23, v45, v46 offset0:16 offset1:82
	ds_write2_b32 v23, v47, v48 offset0:148 offset1:214
	ds_write2_b32 v24, v49, v50 offset0:24 offset1:90
	ds_write2_b32 v24, v51, v52 offset0:156 offset1:222
	ds_write2_b32 v25, v53, v54 offset0:32 offset1:98
	ds_write2_b32 v25, v55, v56 offset0:164 offset1:230
	ds_write2_b32 v36, v57, v58 offset0:40 offset1:106
	ds_write2_b32 v36, v59, v60 offset0:172 offset1:238
	ds_write2_b32 v37, v61, v62 offset0:48 offset1:114
	ds_write2_b32 v37, v63, v64 offset0:180 offset1:246
	ds_write2_b32 v38, v65, v66 offset0:56 offset1:122
	ds_write2_b32 v38, v67, v2 offset0:188 offset1:254
	s_waitcnt lgkmcnt(0)
	ds_read2_b32 v[2:3], v32 offset1:33
	s_waitcnt lgkmcnt(0)
	v_cvt_pk_bf16_f32 v2, v2, v3
	ds_read2_b32 v[4:5], v32 offset0:66 offset1:99
	s_waitcnt lgkmcnt(0)
	v_cvt_pk_bf16_f32 v3, v4, v5
	ds_read2_b32 v[4:5], v32 offset0:132 offset1:165
	s_waitcnt lgkmcnt(0)
	v_cvt_pk_bf16_f32 v4, v4, v5
	ds_read2_b32 v[40:41], v32 offset0:198 offset1:231
	s_waitcnt lgkmcnt(0)
	v_cvt_pk_bf16_f32 v5, v40, v41
	v_add_u32_e32 v40, s4, v31
	v_ashrrev_i32_e32 v41, 31, v40
	v_lshl_add_u64 v[20:21], s[42:43], 1, v[18:19]
	v_lshlrev_b64 v[40:41], 7, v[40:41]
	v_lshl_add_u64 v[40:41], v[20:21], 0, v[40:41]
	global_store_dwordx4 v[40:41], v[2:5], off
	ds_read2_b32 v[2:3], v33 offset1:33
	s_add_i32 s1, s1, s3
	s_waitcnt lgkmcnt(0)
	v_cvt_pk_bf16_f32 v2, v2, v3
	ds_read2_b32 v[4:5], v33 offset0:66 offset1:99
	s_waitcnt lgkmcnt(0)
	v_cvt_pk_bf16_f32 v3, v4, v5
	ds_read2_b32 v[4:5], v33 offset0:132 offset1:165
	s_waitcnt lgkmcnt(0)
	v_cvt_pk_bf16_f32 v4, v4, v5
	ds_read2_b32 v[40:41], v33 offset0:198 offset1:231
	s_waitcnt lgkmcnt(0)
	v_cvt_pk_bf16_f32 v5, v40, v41
	v_add_u32_e32 v40, s4, v27
	v_ashrrev_i32_e32 v41, 31, v40
	v_lshlrev_b64 v[40:41], 7, v[40:41]
	v_lshl_add_u64 v[40:41], v[20:21], 0, v[40:41]
	global_store_dwordx4 v[40:41], v[2:5], off
	ds_read2_b32 v[2:3], v34 offset1:33
	s_add_i32 s23, s23, s24
	s_waitcnt lgkmcnt(0)
	v_cvt_pk_bf16_f32 v2, v2, v3
	ds_read2_b32 v[4:5], v34 offset0:66 offset1:99
	s_waitcnt lgkmcnt(0)
	v_cvt_pk_bf16_f32 v3, v4, v5
	ds_read2_b32 v[4:5], v34 offset0:132 offset1:165
	s_waitcnt lgkmcnt(0)
	v_cvt_pk_bf16_f32 v4, v4, v5
	ds_read2_b32 v[40:41], v34 offset0:198 offset1:231
	s_waitcnt lgkmcnt(0)
	v_cvt_pk_bf16_f32 v5, v40, v41
	v_add_u32_e32 v40, s4, v28
	v_ashrrev_i32_e32 v41, 31, v40
	v_lshlrev_b64 v[40:41], 7, v[40:41]
	v_lshl_add_u64 v[40:41], v[20:21], 0, v[40:41]
	global_store_dwordx4 v[40:41], v[2:5], off
	ds_read2_b32 v[2:3], v35 offset1:33
	s_cmp_gt_i32 s1, 1
	s_waitcnt lgkmcnt(0)
	v_cvt_pk_bf16_f32 v2, v2, v3
	ds_read2_b32 v[4:5], v35 offset0:66 offset1:99
	s_waitcnt lgkmcnt(0)
	v_cvt_pk_bf16_f32 v3, v4, v5
	ds_read2_b32 v[4:5], v35 offset0:132 offset1:165
	s_waitcnt lgkmcnt(0)
	v_cvt_pk_bf16_f32 v4, v4, v5
	ds_read2_b32 v[40:41], v35 offset0:198 offset1:231
	s_waitcnt lgkmcnt(0)
	v_cvt_pk_bf16_f32 v5, v40, v41
	v_add_u32_e32 v40, s4, v29
	v_ashrrev_i32_e32 v41, 31, v40
	v_lshlrev_b64 v[40:41], 7, v[40:41]
	v_lshl_add_u64 v[20:21], v[20:21], 0, v[40:41]
	global_store_dwordx4 v[20:21], v[2:5], off
	s_waitcnt lgkmcnt(0)
	s_cbranch_scc0 .LBB0_1508
	s_branch .LBB0_1503

; __device__ __forceinline__ void p0_transpose_item(const float* W, int K, int N, bf16_t* WT, LAS float* scr, int item, int lane) {
;     const int nblk = N / 32, kb = item / nblk, nb = item % nblk, k0 = 64 * kb, n0 = 32 * nb;
;     float tv[32];
; #pragma unroll
;     for (int i = 0; i < 32; ++i) tv[i] = W[(size_t)(k0 + 2 * i + (lane >> 5)) * N + n0 + (lane & 31)];
.LBB0_1513:
	s_lshr_b32 s4, s18, 31
	s_add_i32 s4, s18, s4
	s_lshl_b32 s4, s4, 5
	s_and_b32 s40, s4, 0xffffffc0
	v_or_b32_e32 v4, s40, v30
	s_sub_i32 s4, s6, s40
	v_or_b32_e32 v20, 2, v4
	s_ashr_i32 s5, s4, 31
	v_ashrrev_i32_e32 v5, 31, v4
	v_ashrrev_i32_e32 v21, 31, v20
	v_lshl_add_u64 v[2:3], s[4:5], 2, v[14:15]
	v_lshlrev_b64 v[18:19], 8, v[4:5]
	v_lshlrev_b64 v[20:21], 8, v[20:21]
	v_lshl_add_u64 v[18:19], v[2:3], 0, v[18:19]
	v_lshl_add_u64 v[20:21], v[2:3], 0, v[20:21]
	global_load_dword v18, v[18:19], off
	v_or_b32_e32 v22, 6, v4
	global_load_dword v19, v[20:21], off
	v_or_b32_e32 v20, 4, v4
	v_ashrrev_i32_e32 v21, 31, v20
	v_ashrrev_i32_e32 v23, 31, v22
	v_lshlrev_b64 v[20:21], 8, v[20:21]
	v_lshlrev_b64 v[22:23], 8, v[22:23]
	v_lshl_add_u64 v[20:21], v[2:3], 0, v[20:21]
	v_lshl_add_u64 v[22:23], v[2:3], 0, v[22:23]
	global_load_dword v20, v[20:21], off
	v_or_b32_e32 v24, 10, v4
	global_load_dword v21, v[22:23], off
	v_or_b32_e32 v22, 8, v4
	v_ashrrev_i32_e32 v23, 31, v22
	v_ashrrev_i32_e32 v25, 31, v24
	v_lshlrev_b64 v[22:23], 8, v[22:23]
	v_lshlrev_b64 v[24:25], 8, v[24:25]
	v_lshl_add_u64 v[22:23], v[2:3], 0, v[22:23]
	v_lshl_add_u64 v[24:25], v[2:3], 0, v[24:25]
	global_load_dword v22, v[22:23], off
	v_or_b32_e32 v36, 14, v4
	global_load_dword v23, v[24:25], off
	v_or_b32_e32 v24, 12, v4
	v_ashrrev_i32_e32 v25, 31, v24
	v_ashrrev_i32_e32 v37, 31, v36
	v_lshlrev_b64 v[24:25], 8, v[24:25]
	v_lshlrev_b64 v[36:37], 8, v[36:37]
	v_lshl_add_u64 v[24:25], v[2:3], 0, v[24:25]
	v_lshl_add_u64 v[36:37], v[2:3], 0, v[36:37]
	global_load_dword v24, v[24:25], off
	v_or_b32_e32 v38, 18, v4
	global_load_dword v25, v[36:37], off
	v_or_b32_e32 v36, 16, v4
	v_ashrrev_i32_e32 v37, 31, v36
	v_ashrrev_i32_e32 v39, 31, v38
	v_lshlrev_b64 v[36:37], 8, v[36:37]
	v_lshlrev_b64 v[38:39], 8, v[38:39]
	v_lshl_add_u64 v[36:37], v[2:3], 0, v[36:37]
	v_lshl_add_u64 v[38:39], v[2:3], 0, v[38:39]
	global_load_dword v36, v[36:37], off
	v_or_b32_e32 v40, 22, v4
	global_load_dword v37, v[38:39], off
	v_or_b32_e32 v38, 20, v4
	v_ashrrev_i32_e32 v39, 31, v38
	v_ashrrev_i32_e32 v41, 31, v40
	v_lshlrev_b64 v[38:39], 8, v[38:39]
	v_lshlrev_b64 v[40:41], 8, v[40:41]
	v_lshl_add_u64 v[38:39], v[2:3], 0, v[38:39]
	v_lshl_add_u64 v[40:41], v[2:3], 0, v[40:41]
	global_load_dword v38, v[38:39], off
	v_or_b32_e32 v42, 26, v4
	global_load_dword v39, v[40:41], off
	v_or_b32_e32 v40, 24, v4
	v_ashrrev_i32_e32 v41, 31, v40
	v_ashrrev_i32_e32 v43, 31, v42
	v_lshlrev_b64 v[40:41], 8, v[40:41]
	v_lshlrev_b64 v[42:43], 8, v[42:43]
	v_lshl_add_u64 v[40:41], v[2:3], 0, v[40:41]
	v_lshl_add_u64 v[42:43], v[2:3], 0, v[42:43]
	global_load_dword v40, v[40:41], off
	v_or_b32_e32 v44, 30, v4
	global_load_dword v41, v[42:43], off
	v_or_b32_e32 v42, 28, v4
	v_ashrrev_i32_e32 v43, 31, v42
	v_ashrrev_i32_e32 v45, 31, v44
	v_lshlrev_b64 v[42:43], 8, v[42:43]
	v_lshlrev_b64 v[44:45], 8, v[44:45]
	v_lshl_add_u64 v[42:43], v[2:3], 0, v[42:43]
	v_lshl_add_u64 v[44:45], v[2:3], 0, v[44:45]
	global_load_dword v42, v[42:43], off
	v_or_b32_e32 v46, 34, v4
	global_load_dword v43, v[44:45], off
	v_or_b32_e32 v44, 32, v4
	v_ashrrev_i32_e32 v45, 31, v44
	v_ashrrev_i32_e32 v47, 31, v46
	v_lshlrev_b64 v[44:45], 8, v[44:45]
	v_lshlrev_b64 v[46:47], 8, v[46:47]
	v_lshl_add_u64 v[44:45], v[2:3], 0, v[44:45]
	v_lshl_add_u64 v[46:47], v[2:3], 0, v[46:47]
	global_load_dword v44, v[44:45], off
	v_or_b32_e32 v48, 38, v4
	global_load_dword v45, v[46:47], off
	v_or_b32_e32 v46, 36, v4
	v_ashrrev_i32_e32 v47, 31, v46
	v_ashrrev_i32_e32 v49, 31, v48
	v_lshlrev_b64 v[46:47], 8, v[46:47]
	v_lshlrev_b64 v[48:49], 8, v[48:49]
	v_lshl_add_u64 v[46:47], v[2:3], 0, v[46:47]
	v_lshl_add_u64 v[48:49], v[2:3], 0, v[48:49]
	global_load_dword v46, v[46:47], off
	v_or_b32_e32 v50, 42, v4
	global_load_dword v47, v[48:49], off
	v_or_b32_e32 v48, 40, v4
	v_ashrrev_i32_e32 v49, 31, v48
	v_ashrrev_i32_e32 v51, 31, v50
	v_lshlrev_b64 v[48:49], 8, v[48:49]
	v_lshlrev_b64 v[50:51], 8, v[50:51]
	v_lshl_add_u64 v[48:49], v[2:3], 0, v[48:49]
	v_lshl_add_u64 v[50:51], v[2:3], 0, v[50:51]
	global_load_dword v48, v[48:49], off
	v_or_b32_e32 v52, 46, v4
	global_load_dword v49, v[50:51], off
	v_or_b32_e32 v50, 44, v4
	v_ashrrev_i32_e32 v51, 31, v50
	v_ashrrev_i32_e32 v53, 31, v52
	v_lshlrev_b64 v[50:51], 8, v[50:51]
	v_lshlrev_b64 v[52:53], 8, v[52:53]
	v_lshl_add_u64 v[50:51], v[2:3], 0, v[50:51]
	v_lshl_add_u64 v[52:53], v[2:3], 0, v[52:53]
	global_load_dword v50, v[50:51], off
	v_or_b32_e32 v54, 50, v4
	global_load_dword v51, v[52:53], off
	v_or_b32_e32 v52, 48, v4
	v_ashrrev_i32_e32 v53, 31, v52
	v_ashrrev_i32_e32 v55, 31, v54
	v_lshlrev_b64 v[52:53], 8, v[52:53]
	v_lshlrev_b64 v[54:55], 8, v[54:55]
	v_lshl_add_u64 v[52:53], v[2:3], 0, v[52:53]
	v_lshl_add_u64 v[54:55], v[2:3], 0, v[54:55]
	global_load_dword v52, v[52:53], off
	v_or_b32_e32 v56, 54, v4
	global_load_dword v53, v[54:55], off
	v_or_b32_e32 v54, 52, v4
	v_ashrrev_i32_e32 v55, 31, v54
	v_ashrrev_i32_e32 v57, 31, v56
	v_lshlrev_b64 v[54:55], 8, v[54:55]
	v_lshlrev_b64 v[56:57], 8, v[56:57]
	v_lshl_add_u64 v[54:55], v[2:3], 0, v[54:55]
	v_lshl_add_u64 v[56:57], v[2:3], 0, v[56:57]
	global_load_dword v54, v[54:55], off
	v_or_b32_e32 v58, 58, v4
	global_load_dword v55, v[56:57], off
	v_or_b32_e32 v56, 56, v4
	v_ashrrev_i32_e32 v57, 31, v56
	v_ashrrev_i32_e32 v59, 31, v58
	v_lshlrev_b64 v[56:57], 8, v[56:57]
	v_lshlrev_b64 v[58:59], 8, v[58:59]
	v_lshl_add_u64 v[56:57], v[2:3], 0, v[56:57]
	v_lshl_add_u64 v[58:59], v[2:3], 0, v[58:59]
	global_load_dword v56, v[56:57], off
	s_ashr_i32 s41, s40, 31
	global_load_dword v57, v[58:59], off
	v_or_b32_e32 v58, 60, v4
	v_or_b32_e32 v4, 62, v4
	v_ashrrev_i32_e32 v59, 31, v58
	v_ashrrev_i32_e32 v5, 31, v4
	v_lshlrev_b64 v[58:59], 8, v[58:59]
	v_lshlrev_b64 v[4:5], 8, v[4:5]
	v_lshl_add_u64 v[58:59], v[2:3], 0, v[58:59]
	v_lshl_add_u64 v[2:3], v[2:3], 0, v[4:5]
	global_load_dword v58, v[58:59], off
	s_add_i32 s18, s18, s3
	global_load_dword v2, v[2:3], off
	v_add_u32_e32 v3, 0x400, v0
	s_waitcnt vmcnt(0)
; #define LAS __attribute__((address_space(3)))
; __device__ __forceinline__ unsigned cvt_pk_bf16(float lo, float hi) { unsigned r; asm volatile("v_cvt_pk_bf16_f32 %0, %1, %2" : "=v"(r) : "v"(lo), "v"(hi)); return r; }
; __device__ __forceinline__ void p0_transpose_item(const float* W, int K, int N, bf16_t* WT, LAS float* scr, int item, int lane) {
;     ...
;     for (int i = 0; i < 32; ++i) scr[(2 * i + (lane >> 5)) * 33 + (lane & 31)] = tv[i];
;     asm volatile("s_waitcnt lgkmcnt(0)" ::: "memory");
;     const int c = lane & 7;
; #pragma unroll
;     for (int j = 0; j < 4; ++j) { const int n = (lane >> 3) + 8 * j; const LAS float* s = scr + (8 * c) * 33 + n;
;         u32x4 o; o.x = cvt_pk_bf16(s[0 * 33], s[1 * 33]); o.y = cvt_pk_bf16(s[2 * 33], s[3 * 33]); o.z = cvt_pk_bf16(s[4 * 33], s[5 * 33]); o.w = cvt_pk_bf16(s[6 * 33], s[7 * 33]);
;         *(u32x4*)(WT + (size_t)(n0 + n) * K + k0 + 8 * c) = o; }
;     asm volatile("s_waitcnt lgkmcnt(0)" ::: "memory");
	ds_write2_b32 v0, v18, v19 offset1:66
	ds_write2_b32 v0, v20, v21 offset0:132 offset1:198
	ds_write2_b32 v3, v22, v23 offset0:8 offset1:74
	ds_write2_b32 v3, v24, v25 offset0:140 offset1:206
	v_add_u32_e32 v3, 0x800, v0
	ds_write2_b32 v3, v36, v37 offset0:16 offset1:82
	ds_write2_b32 v3, v38, v39 offset0:148 offset1:214
	v_add_u32_e32 v3, 0xc00, v0
	ds_write2_b32 v3, v40, v41 offset0:24 offset1:90
	ds_write2_b32 v3, v42, v43 offset0:156 offset1:222
	v_add_u32_e32 v3, 0x1000, v0
	ds_write2_b32 v3, v44, v45 offset0:32 offset1:98
	ds_write2_b32 v3, v46, v47 offset0:164 offset1:230
	v_add_u32_e32 v3, 0x1400, v0
	ds_write2_b32 v3, v48, v49 offset0:40 offset1:106
	ds_write2_b32 v3, v50, v51 offset0:172 offset1:238
	v_add_u32_e32 v3, 0x1800, v0
	ds_write2_b32 v3, v52, v53 offset0:48 offset1:114
	ds_write2_b32 v3, v54, v55 offset0:180 offset1:246
	v_add_u32_e32 v3, 0x1c00, v0
	ds_write2_b32 v3, v56, v57 offset0:56 offset1:122
	ds_write2_b32 v3, v58, v2 offset0:188 offset1:254
	s_waitcnt lgkmcnt(0)
	ds_read2_b32 v[2:3], v32 offset1:33
	s_waitcnt lgkmcnt(0)
	v_cvt_pk_bf16_f32 v2, v2, v3
	ds_read2_b32 v[4:5], v32 offset0:66 offset1:99
	s_waitcnt lgkmcnt(0)
	v_cvt_pk_bf16_f32 v3, v4, v5
	ds_read2_b32 v[4:5], v32 offset0:132 offset1:165
	s_waitcnt lgkmcnt(0)
	v_cvt_pk_bf16_f32 v4, v4, v5
	ds_read2_b32 v[20:21], v32 offset0:198 offset1:231
	s_waitcnt lgkmcnt(0)
	v_cvt_pk_bf16_f32 v5, v20, v21
	v_add_u32_e32 v20, s4, v31
	v_ashrrev_i32_e32 v21, 31, v20
	v_lshl_add_u64 v[18:19], s[40:41], 1, v[16:17]
	v_lshlrev_b64 v[20:21], 7, v[20:21]
	v_lshl_add_u64 v[20:21], v[18:19], 0, v[20:21]
	global_store_dwordx4 v[20:21], v[2:5], off
	ds_read2_b32 v[2:3], v33 offset1:33
	s_add_i32 s6, s6, s7
	s_waitcnt lgkmcnt(0)
	v_cvt_pk_bf16_f32 v2, v2, v3
	ds_read2_b32 v[4:5], v33 offset0:66 offset1:99
	s_waitcnt lgkmcnt(0)
	v_cvt_pk_bf16_f32 v3, v4, v5
	ds_read2_b32 v[4:5], v33 offset0:132 offset1:165
	s_waitcnt lgkmcnt(0)
	v_cvt_pk_bf16_f32 v4, v4, v5
	ds_read2_b32 v[20:21], v33 offset0:198 offset1:231
	s_waitcnt lgkmcnt(0)
	v_cvt_pk_bf16_f32 v5, v20, v21
	v_add_u32_e32 v20, s4, v27
	v_ashrrev_i32_e32 v21, 31, v20
	v_lshlrev_b64 v[20:21], 7, v[20:21]
	v_lshl_add_u64 v[20:21], v[18:19], 0, v[20:21]
	global_store_dwordx4 v[20:21], v[2:5], off
	ds_read2_b32 v[2:3], v34 offset1:33
	s_cmp_gt_i32 s18, 1
	s_waitcnt lgkmcnt(0)
	v_cvt_pk_bf16_f32 v2, v2, v3
	ds_read2_b32 v[4:5], v34 offset0:66 offset1:99
	s_waitcnt lgkmcnt(0)
	v_cvt_pk_bf16_f32 v3, v4, v5
	ds_read2_b32 v[4:5], v34 offset0:132 offset1:165
	s_waitcnt lgkmcnt(0)
	v_cvt_pk_bf16_f32 v4, v4, v5
	ds_read2_b32 v[20:21], v34 offset0:198 offset1:231
	s_waitcnt lgkmcnt(0)
	v_cvt_pk_bf16_f32 v5, v20, v21
	v_add_u32_e32 v20, s4, v28
	v_ashrrev_i32_e32 v21, 31, v20
	v_lshlrev_b64 v[20:21], 7, v[20:21]
	v_lshl_add_u64 v[20:21], v[18:19], 0, v[20:21]
	global_store_dwordx4 v[20:21], v[2:5], off
	ds_read2_b32 v[2:3], v35 offset1:33
	s_waitcnt lgkmcnt(0)
	v_cvt_pk_bf16_f32 v2, v2, v3
	ds_read2_b32 v[4:5], v35 offset0:66 offset1:99
	s_waitcnt lgkmcnt(0)
	v_cvt_pk_bf16_f32 v3, v4, v5
	ds_read2_b32 v[4:5], v35 offset0:132 offset1:165
	s_waitcnt lgkmcnt(0)
	v_cvt_pk_bf16_f32 v4, v4, v5
	ds_read2_b32 v[20:21], v35 offset0:198 offset1:231
	s_waitcnt lgkmcnt(0)
	v_cvt_pk_bf16_f32 v5, v20, v21
	v_add_u32_e32 v20, s4, v29
	v_ashrrev_i32_e32 v21, 31, v20
	v_lshlrev_b64 v[20:21], 7, v[20:21]
	v_lshl_add_u64 v[18:19], v[18:19], 0, v[20:21]
	global_store_dwordx4 v[18:19], v[2:5], off
	s_waitcnt lgkmcnt(0)
	s_cbranch_scc0 .LBB0_1513
	s_branch .LBB0_1510

.LBB0_1516:
	v_add_u32_e32 v0, 0x1c000, v0
	s_mov_b32 s1, 0xfffe6fff
	v_cmp_lt_i32_e32 vcc, s1, v0
	s_mov_b64 s[6:7], 0x1c0000
	global_store_dwordx4 v[2:3], v[10:13], off
	s_or_b64 s[20:21], vcc, s[20:21]
	v_lshl_add_u64 v[2:3], v[2:3], 0, s[6:7]
	s_andn2_b64 exec, exec, s[20:21]
	s_cbranch_execnz .LBB0_1516

;     __device__ __forceinline__ bool operator()(f32x4 (&acc)[2][2][4][2], const Unit& u, int wr, int wc, int fr, int fq) const {
;         const int row0 = u.pm * BM + wr * 64 + fr, col0 = u.pn * BM + wc * 32 + 8 * fq;
;         const bool isc = u.pm * BM >= ML; const int rr0 = isc ? row0 - ML : row0;
;         const float* src = (isc ? xci : xi) + (size_t)rr0 * 1024 + col0; float* dst = (isc ? xco : xo) + (size_t)rr0 * 1024 + col0;
;         const float* gp = gate + (size_t)(isc ? 16 : (bofs + ((u.pm * BM) >> 11))) * 3072 + col0;
;         f32x4 g[2][2];
; #pragma unroll
;         for (int bj = 0; bj < 2; ++bj) { g[bj][0] = *(const f32x4*)(gp + bj * HALF); g[bj][1] = *(const f32x4*)(gp + bj * HALF + 4); }
; #pragma unroll
;         for (int aim = 0; aim < 4; ++aim) { const int ai = aim >> 1, mh = (aim & 1) * 2;
;             f32x4 xv[2][2][2];
; #pragma unroll
;             for (int m = 0; m < 2; ++m)
; #pragma unroll
;                 for (int bj = 0; bj < 2; ++bj) { const float* sp = src + (size_t)(ai * HALF + (mh + m) * 16) * 1024 + bj * HALF; xv[m][bj][0] = *(const f32x4*)sp; xv[m][bj][1] = *(const f32x4*)(sp + 4); }
; #pragma unroll
;             for (int m = 0; m < 2; ++m)
; #pragma unroll
;                 for (int bj = 0; bj < 2; ++bj) { float* dp = dst + (size_t)(ai * HALF + (mh + m) * 16) * 1024 + bj * HALF;
;                     *(f32x4*)dp = xv[m][bj][0] + g[bj][0] * acc[ai][bj][mh + m][0]; *(f32x4*)(dp + 4) = xv[m][bj][1] + g[bj][1] * acc[ai][bj][mh + m][1]; }
.LBB0_1582:
	s_and_b64 s[14:15], exec, s[22:23]
	v_ashrrev_i32_e32 v111, 31, v110
	s_cselect_b32 s15, s51, s31
	s_cselect_b32 s14, s50, s30
	s_cselect_b32 s23, s53, s34
	s_cselect_b32 s22, s52, s33
	v_lshlrev_b64 v[110:111], 12, v[110:111]
	v_lshl_add_u64 v[112:113], s[22:23], 0, v[110:111]
	v_lshl_or_b32 v118, s59, 8, v172
	v_lshl_add_u64 v[110:111], s[14:15], 0, v[110:111]
	s_lshl_b64 s[14:15], s[20:21], 2
	v_ashrrev_i32_e32 v119, 31, v118
	s_add_u32 s14, s54, s14
	v_lshlrev_b64 v[118:119], 2, v[118:119]
	s_addc_u32 s15, s55, s15
	v_lshl_add_u64 v[168:169], v[110:111], 0, v[118:119]
	v_lshl_add_u64 v[110:111], s[14:15], 0, v[118:119]
	s_mov_b32 s14, 0x10000
	v_add_co_u32_e32 v222, vcc, s14, v168
	v_lshl_add_u64 v[166:167], v[112:113], 0, v[118:119]
	global_load_dwordx4 v[130:133], v[110:111], off
	global_load_dwordx4 v[122:125], v[110:111], off offset:16
	global_load_dwordx4 v[118:121], v[110:111], off offset:512
	s_nop 0
	global_load_dwordx4 v[110:113], v[110:111], off offset:528
	s_nop 0
	global_load_dwordx4 v[174:177], v[168:169], off
	global_load_dwordx4 v[178:181], v[168:169], off offset:16
	global_load_dwordx4 v[182:185], v[168:169], off offset:512
	global_load_dwordx4 v[186:189], v[168:169], off offset:528
	v_addc_co_u32_e32 v223, vcc, 0, v169, vcc
	global_load_dwordx4 v[190:193], v[222:223], off
	global_load_dwordx4 v[214:217], v[222:223], off offset:16
	global_load_dwordx4 v[218:221], v[222:223], off offset:512
	s_nop 0
	global_load_dwordx4 v[222:225], v[222:223], off offset:528
	s_mov_b64 s[64:65], 0x100
	s_waitcnt vmcnt(0) lgkmcnt(0)
	v_pk_fma_f32 v[148:149], v[148:149], v[132:133], v[176:177]
	v_pk_fma_f32 v[146:147], v[146:147], v[130:131], v[174:175]
	v_pk_fma_f32 v[136:137], v[136:137], v[120:121], v[184:185]
	v_pk_fma_f32 v[134:135], v[134:135], v[118:119], v[182:183]
	global_store_dwordx4 v[166:167], v[134:137], off offset:512
	v_pk_fma_f32 v[128:129], v[128:129], v[112:113], v[188:189]
	v_pk_fma_f32 v[126:127], v[126:127], v[110:111], v[186:187]
	v_add_co_u32_e32 v134, vcc, s14, v166
	v_pk_fma_f32 v[144:145], v[144:145], v[124:125], v[180:181]
	v_pk_fma_f32 v[142:143], v[142:143], v[122:123], v[178:179]
	global_store_dwordx4 v[166:167], v[126:129], off offset:528
	v_addc_co_u32_e32 v135, vcc, 0, v167, vcc
	s_nop 0
	v_pk_fma_f32 v[128:129], v[140:141], v[132:133], v[192:193]
	v_pk_fma_f32 v[126:127], v[138:139], v[130:131], v[190:191]
	v_pk_fma_f32 v[116:117], v[116:117], v[124:125], v[216:217]
	v_pk_fma_f32 v[114:115], v[114:115], v[122:123], v[214:215]
	v_pk_fma_f32 v[108:109], v[108:109], v[120:121], v[220:221]
	v_pk_fma_f32 v[106:107], v[106:107], v[118:119], v[218:219]
	v_pk_fma_f32 v[104:105], v[104:105], v[112:113], v[224:225]
	v_pk_fma_f32 v[102:103], v[102:103], v[110:111], v[222:223]
	global_store_dwordx4 v[166:167], v[146:149], off
	global_store_dwordx4 v[166:167], v[142:145], off offset:16
	global_store_dwordx4 v[134:135], v[126:129], off
	global_store_dwordx4 v[134:135], v[114:117], off offset:16
	global_store_dwordx4 v[134:135], v[106:109], off offset:512
	global_store_dwordx4 v[134:135], v[102:105], off offset:528
	s_mov_b32 s15, 0x20000
	v_add_co_u32_e32 v126, vcc, s15, v168
	s_mov_b32 s14, 0x30000
	s_nop 0
	v_addc_co_u32_e32 v127, vcc, 0, v169, vcc
	v_add_co_u32_e32 v146, vcc, s14, v168
	global_load_dwordx4 v[102:105], v[126:127], off
	global_load_dwordx4 v[106:109], v[126:127], off offset:16
	global_load_dwordx4 v[114:117], v[126:127], off offset:512
	s_nop 0
	global_load_dwordx4 v[126:129], v[126:127], off offset:528
	v_addc_co_u32_e32 v147, vcc, 0, v169, vcc
	global_load_dwordx4 v[134:137], v[146:147], off
	global_load_dwordx4 v[138:141], v[146:147], off offset:16
	global_load_dwordx4 v[142:145], v[146:147], off offset:512
	s_nop 0
	global_load_dwordx4 v[146:149], v[146:147], off offset:528
	s_waitcnt vmcnt(0) lgkmcnt(0)
;     __device__ __forceinline__ bool operator()(f32x4 (&acc)[2][2][4][2], const Unit& u, int wr, int wc, int fr, int fq) const {
;     ...
;         for (int aim = 0; aim < 4; ++aim) { const int ai = aim >> 1, mh = (aim & 1) * 2;
;             f32x4 xv[2][2][2];
; #pragma unroll
;             for (int m = 0; m < 2; ++m)
; #pragma unroll
;                 for (int bj = 0; bj < 2; ++bj) { const float* sp = src + (size_t)(ai * HALF + (mh + m) * 16) * 1024 + bj * HALF; xv[m][bj][0] = *(const f32x4*)sp; xv[m][bj][1] = *(const f32x4*)(sp + 4); }
; #pragma unroll
;             for (int m = 0; m < 2; ++m)
; #pragma unroll
;                 for (int bj = 0; bj < 2; ++bj) { float* dp = dst + (size_t)(ai * HALF + (mh + m) * 16) * 1024 + bj * HALF;
;                     *(f32x4*)dp = xv[m][bj][0] + g[bj][0] * acc[ai][bj][mh + m][0]; *(f32x4*)(dp + 4) = xv[m][bj][1] + g[bj][1] * acc[ai][bj][mh + m][1]; }
;             __builtin_amdgcn_sched_barrier(0);
;         }
;         return false;
	v_pk_fma_f32 v[98:99], v[98:99], v[130:131], v[102:103]
	v_add_co_u32_e32 v102, vcc, s15, v166
	v_pk_fma_f32 v[88:89], v[88:89], v[120:121], v[116:117]
	s_nop 0
	v_addc_co_u32_e32 v103, vcc, 0, v167, vcc
	v_pk_fma_f32 v[86:87], v[86:87], v[118:119], v[114:115]
	global_store_dwordx4 v[102:103], v[86:89], off offset:512
	v_pk_fma_f32 v[84:85], v[84:85], v[112:113], v[128:129]
	v_pk_fma_f32 v[82:83], v[82:83], v[110:111], v[126:127]
	v_add_co_u32_e32 v86, vcc, s14, v166
	v_pk_fma_f32 v[100:101], v[100:101], v[132:133], v[104:105]
	v_pk_fma_f32 v[96:97], v[96:97], v[124:125], v[108:109]
	v_pk_fma_f32 v[94:95], v[94:95], v[122:123], v[106:107]
	global_store_dwordx4 v[102:103], v[82:85], off offset:528
	v_addc_co_u32_e32 v87, vcc, 0, v167, vcc
	s_nop 0
	v_pk_fma_f32 v[84:85], v[92:93], v[132:133], v[136:137]
	v_pk_fma_f32 v[82:83], v[90:91], v[130:131], v[134:135]
	v_pk_fma_f32 v[80:81], v[80:81], v[124:125], v[140:141]
	v_pk_fma_f32 v[78:79], v[78:79], v[122:123], v[138:139]
	v_pk_fma_f32 v[76:77], v[76:77], v[120:121], v[144:145]
	v_pk_fma_f32 v[74:75], v[74:75], v[118:119], v[142:143]
	v_pk_fma_f32 v[72:73], v[72:73], v[112:113], v[148:149]
	v_pk_fma_f32 v[70:71], v[70:71], v[110:111], v[146:147]
	global_store_dwordx4 v[102:103], v[98:101], off
	global_store_dwordx4 v[102:103], v[94:97], off offset:16
	global_store_dwordx4 v[86:87], v[82:85], off
	global_store_dwordx4 v[86:87], v[78:81], off offset:16
	global_store_dwordx4 v[86:87], v[74:77], off offset:512
	global_store_dwordx4 v[86:87], v[70:73], off offset:528
	s_mov_b32 s14, 0x80000
	v_add_co_u32_e32 v82, vcc, s14, v168
	s_mov_b32 s15, 0x90000
	s_nop 0
	v_addc_co_u32_e32 v83, vcc, 0, v169, vcc
	v_add_co_u32_e32 v98, vcc, s15, v168
	global_load_dwordx4 v[70:73], v[82:83], off
	global_load_dwordx4 v[74:77], v[82:83], off offset:16
	global_load_dwordx4 v[78:81], v[82:83], off offset:512
	s_nop 0
	global_load_dwordx4 v[82:85], v[82:83], off offset:528
	v_addc_co_u32_e32 v99, vcc, 0, v169, vcc
	global_load_dwordx4 v[86:89], v[98:99], off
	global_load_dwordx4 v[90:93], v[98:99], off offset:16
	global_load_dwordx4 v[94:97], v[98:99], off offset:512
	s_nop 0
	global_load_dwordx4 v[98:101], v[98:99], off offset:528
	s_waitcnt vmcnt(0) lgkmcnt(0)
	v_pk_fma_f32 v[66:67], v[66:67], v[130:131], v[70:71]
	v_add_co_u32_e32 v70, vcc, s14, v166
	v_pk_fma_f32 v[56:57], v[56:57], v[120:121], v[80:81]
	s_nop 0
	v_addc_co_u32_e32 v71, vcc, 0, v167, vcc
	v_pk_fma_f32 v[54:55], v[54:55], v[118:119], v[78:79]
	global_store_dwordx4 v[70:71], v[54:57], off offset:512
	v_pk_fma_f32 v[52:53], v[52:53], v[112:113], v[84:85]
	v_pk_fma_f32 v[50:51], v[50:51], v[110:111], v[82:83]
	v_add_co_u32_e32 v54, vcc, s15, v166
	v_pk_fma_f32 v[68:69], v[68:69], v[132:133], v[72:73]
	v_pk_fma_f32 v[64:65], v[64:65], v[124:125], v[76:77]
	v_pk_fma_f32 v[62:63], v[62:63], v[122:123], v[74:75]
	global_store_dwordx4 v[70:71], v[50:53], off offset:528
	v_addc_co_u32_e32 v55, vcc, 0, v167, vcc
	s_nop 0
	v_pk_fma_f32 v[52:53], v[60:61], v[132:133], v[88:89]
	v_pk_fma_f32 v[50:51], v[58:59], v[130:131], v[86:87]
	v_pk_fma_f32 v[48:49], v[48:49], v[124:125], v[92:93]
	v_pk_fma_f32 v[46:47], v[46:47], v[122:123], v[90:91]
	v_pk_fma_f32 v[44:45], v[44:45], v[120:121], v[96:97]
	v_pk_fma_f32 v[42:43], v[42:43], v[118:119], v[94:95]
	v_pk_fma_f32 v[40:41], v[40:41], v[112:113], v[100:101]
	v_pk_fma_f32 v[38:39], v[38:39], v[110:111], v[98:99]
	global_store_dwordx4 v[70:71], v[66:69], off
	global_store_dwordx4 v[70:71], v[62:65], off offset:16
	global_store_dwordx4 v[54:55], v[50:53], off
	global_store_dwordx4 v[54:55], v[46:49], off offset:16
	global_store_dwordx4 v[54:55], v[42:45], off offset:512
	global_store_dwordx4 v[54:55], v[38:41], off offset:528
	s_mov_b32 s14, 0xa0000
	v_add_co_u32_e32 v50, vcc, s14, v168
	s_mov_b32 s15, 0xb0000
	s_nop 0
	v_addc_co_u32_e32 v51, vcc, 0, v169, vcc
	v_add_co_u32_e32 v66, vcc, s15, v168
	global_load_dwordx4 v[38:41], v[50:51], off
	global_load_dwordx4 v[42:45], v[50:51], off offset:16
	global_load_dwordx4 v[46:49], v[50:51], off offset:512
	s_nop 0
	global_load_dwordx4 v[50:53], v[50:51], off offset:528
	v_addc_co_u32_e32 v67, vcc, 0, v169, vcc
	global_load_dwordx4 v[54:57], v[66:67], off
	global_load_dwordx4 v[58:61], v[66:67], off offset:16
	global_load_dwordx4 v[62:65], v[66:67], off offset:512
	s_nop 0
	global_load_dwordx4 v[66:69], v[66:67], off offset:528
	s_waitcnt vmcnt(0) lgkmcnt(0)
	v_pk_fma_f32 v[34:35], v[34:35], v[130:131], v[38:39]
	v_add_co_u32_e32 v38, vcc, s14, v166
	v_pk_fma_f32 v[24:25], v[24:25], v[120:121], v[48:49]
	s_nop 0
	v_addc_co_u32_e32 v39, vcc, 0, v167, vcc
	v_pk_fma_f32 v[22:23], v[22:23], v[118:119], v[46:47]
	global_store_dwordx4 v[38:39], v[22:25], off offset:512
	v_pk_fma_f32 v[20:21], v[20:21], v[112:113], v[52:53]
	v_pk_fma_f32 v[18:19], v[18:19], v[110:111], v[50:51]
	v_add_co_u32_e32 v22, vcc, s15, v166
	v_pk_fma_f32 v[36:37], v[36:37], v[132:133], v[40:41]
	v_pk_fma_f32 v[32:33], v[32:33], v[124:125], v[44:45]
	v_pk_fma_f32 v[30:31], v[30:31], v[122:123], v[42:43]
	global_store_dwordx4 v[38:39], v[18:21], off offset:528
	v_addc_co_u32_e32 v23, vcc, 0, v167, vcc
	s_nop 0
	v_pk_fma_f32 v[20:21], v[28:29], v[132:133], v[56:57]
	v_pk_fma_f32 v[18:19], v[26:27], v[130:131], v[54:55]
	v_pk_fma_f32 v[16:17], v[16:17], v[124:125], v[60:61]
	v_pk_fma_f32 v[14:15], v[14:15], v[122:123], v[58:59]
	v_pk_fma_f32 v[8:9], v[8:9], v[120:121], v[64:65]
	v_pk_fma_f32 v[6:7], v[6:7], v[118:119], v[62:63]
	v_pk_fma_f32 v[4:5], v[4:5], v[112:113], v[68:69]
	v_pk_fma_f32 v[2:3], v[2:3], v[110:111], v[66:67]
	global_store_dwordx4 v[38:39], v[34:37], off
	global_store_dwordx4 v[38:39], v[30:33], off offset:16
	global_store_dwordx4 v[22:23], v[18:21], off
	global_store_dwordx4 v[22:23], v[14:17], off offset:16
	global_store_dwordx4 v[22:23], v[6:9], off offset:512
	global_store_dwordx4 v[22:23], v[2:5], off offset:528
	s_andn2_b64 vcc, exec, s[36:37]
	s_mov_b64 s[20:21], -1
	s_cbranch_vccnz .LBB0_1572
	s_andn2_b64 vcc, exec, s[4:5]
	s_cbranch_vccnz .LBB0_1571
	s_barrier
	s_branch .LBB0_1571

; __device__ __forceinline__ unsigned cvt_pk_bf16(float lo, float hi) { unsigned r; asm volatile("v_cvt_pk_bf16_f32 %0, %1, %2" : "=v"(r) : "v"(lo), "v"(hi)); return r; }
; __device__ __forceinline__ float wave_sum(float v) {
; #pragma unroll
;     for (int o = 1; o < 64; o <<= 1) v += __shfl_xor(v, o);
;     return v;
; }
; __global__ void __launch_bounds__(512, 2) fwd_kernel(KArgs a) {
;     ...
;             for (int row = gw; row < MH; row += NGW) {
;                 const bool isc = row >= ML; const int rr = isc ? row - ML : row;
;                 const float* xr = (isc ? xcin : xin) + (size_t)rr * 1024;
;                 const float* md = modl + (size_t)(isc ? 16 : hf * HB + (row >> 11)) * 3072;
;                 const float* ng = a.in[6] + l * 1024;
;                 f32x4 v[4]; float ss = 0.f;
; #pragma unroll
;                 for (int j = 0; j < 4; ++j) { v[j] = *(const f32x4*)(xr + 4 * lane + 256 * j); ss += (v[j][0] * v[j][0] + v[j][1] * v[j][1]) + (v[j][2] * v[j][2] + v[j][3] * v[j][3]); }
;                 const float rinv = rsqrtf(wave_sum(ss) * (1.f / 1024.f) + EPS);
; #pragma unroll
;                 for (int j = 0; j < 4; ++j) { const int c = 4 * lane + 256 * j; const f32x4 gg = *(const f32x4*)(ng + c), sh = *(const f32x4*)(md + c), sc = *(const f32x4*)(md + 1024 + c);
;                     const f32x4 o = v[j] * rinv * gg * (sc + 1.f) + sh; u32x2 w; w.x = cvt_pk_bf16(o[0], o[1]); w.y = cvt_pk_bf16(o[2], o[3]);
;                     *(u32x2*)(HZ + (size_t)row * 1024 + c) = w; }
;             } }
.LBB0_1589:
	s_add_i32 s25, s1, 0xffffc000
	s_and_b64 s[14:15], exec, s[20:21]
	s_cselect_b32 s14, s25, s1
	s_cselect_b32 s20, s22, s7
	s_cselect_b32 s21, s19, s6
	s_ashr_i32 s15, s14, 31
	s_lshl_b64 s[14:15], s[14:15], 12
	s_add_u32 s14, s21, s14
	s_addc_u32 s15, s20, s15
	v_lshl_add_u64 v[2:3], s[14:15], 0, v[0:1]
	global_load_dwordx4 v[18:21], v[2:3], off
	global_load_dwordx4 v[14:17], v[2:3], off offset:1024
	s_lshl_b64 s[4:5], s[4:5], 2
	s_add_u32 s20, s23, s4
	s_addc_u32 s21, s24, s5
	s_add_u32 s4, s20, 0x1000
	s_addc_u32 s5, s21, 0
	v_lshl_add_u64 v[50:51], s[4:5], 0, v[0:1]
	s_add_i32 s1, s1, s55
	s_cmpk_lt_i32 s1, 0x4800
	s_waitcnt vmcnt(0) lgkmcnt(0)
	v_pk_mul_f32 v[4:5], v[20:21], v[20:21]
	v_pk_mul_f32 v[6:7], v[18:19], v[18:19]
	s_nop 0
	v_pk_mov_b32 v[8:9], v[6:7], v[4:5] op_sel:[1,0]
	v_mov_b32_e32 v7, v5
	v_pk_add_f32 v[22:23], v[8:9], v[6:7]
	v_pk_mul_f32 v[4:5], v[16:17], v[16:17]
	v_pk_mul_f32 v[6:7], v[14:15], v[14:15]
	v_pk_add_f32 v[22:23], v[22:23], v[22:23] op_sel:[0,1] op_sel_hi:[1,0]
	v_pk_mov_b32 v[8:9], v[6:7], v[4:5] op_sel:[1,0]
	v_mov_b32_e32 v7, v5
	v_pk_add_f32 v[24:25], v[8:9], v[6:7]
	global_load_dwordx4 v[6:9], v[2:3], off offset:2048
	s_nop 0
	global_load_dwordx4 v[2:5], v[2:3], off offset:3072
	v_pk_add_f32 v[24:25], v[24:25], v[24:25] op_sel:[0,1] op_sel_hi:[1,0]
	global_load_dwordx4 v[50:53], v[50:51], off
	s_waitcnt vmcnt(0) lgkmcnt(0)
	v_mul_f32_e32 v36, v9, v9
	v_mul_f32_e32 v31, v2, v2
	v_mul_f32_e32 v33, v3, v3
	v_mov_b32_e32 v23, v31
	v_mov_b32_e32 v25, v33
	v_pk_add_f32 v[22:23], v[22:23], v[24:25]
	v_mul_f32_e32 v24, v7, v7
	v_mul_f32_e32 v35, v4, v4
	v_mul_f32_e32 v45, v5, v5
	v_pk_fma_f32 v[24:25], v[6:7], v[6:7], v[24:25] op_sel_hi:[1,1,0]
	v_pk_fma_f32 v[38:39], v[8:9], v[8:9], v[36:37] op_sel_hi:[1,1,0]
	v_mov_b32_e32 v25, v35
	v_mov_b32_e32 v39, v45
	v_pk_add_f32 v[24:25], v[24:25], v[38:39]
	v_lshl_add_u64 v[38:39], s[20:21], 0, v[0:1]
	v_pk_add_f32 v[22:23], v[22:23], v[24:25]
	global_load_dwordx4 v[46:49], v[38:39], off
	v_add_f32_e32 v22, v22, v23
	ds_bpermute_b32 v23, v37, v22
	v_mov_b32_e32 v31, v1
	v_mov_b32_e32 v33, v1
	v_mov_b32_e32 v35, v1
	s_waitcnt lgkmcnt(0)
	v_add_f32_e32 v22, v22, v23
	ds_bpermute_b32 v23, v40, v22
	s_waitcnt lgkmcnt(0)
	v_add_f32_e32 v22, v22, v23
	ds_bpermute_b32 v23, v41, v22
	s_waitcnt lgkmcnt(0)
	v_add_f32_e32 v22, v22, v23
	ds_bpermute_b32 v23, v42, v22
	s_waitcnt lgkmcnt(0)
	v_add_f32_e32 v22, v22, v23
	ds_bpermute_b32 v23, v43, v22
	s_waitcnt lgkmcnt(0)
	v_add_f32_e32 v22, v22, v23
	ds_bpermute_b32 v23, v44, v22
	s_waitcnt lgkmcnt(0)
	v_add_f32_e32 v22, v22, v23
	v_fmamk_f32 v22, v22, 0x3a800000, v197
	v_cmp_gt_f32_e32 vcc, s26, v22
	v_mul_f32_e32 v23, 0x4b800000, v22
	s_nop 0
	v_cndmask_b32_e32 v22, v22, v23, vcc
	v_rsq_f32_e32 v22, v22
	s_nop 0
	v_mul_f32_e32 v23, 0x45800000, v22
	v_cndmask_b32_e32 v36, v22, v23, vcc
	global_load_dwordx4 v[22:25], v[26:27], off
	v_pk_mul_f32 v[20:21], v[36:37], v[20:21] op_sel_hi:[0,1]
	v_pk_mul_f32 v[18:19], v[36:37], v[18:19] op_sel_hi:[0,1]
	v_pk_mul_f32 v[16:17], v[36:37], v[16:17] op_sel_hi:[0,1]
	v_pk_mul_f32 v[14:15], v[36:37], v[14:15] op_sel_hi:[0,1]
	v_pk_mul_f32 v[8:9], v[36:37], v[8:9] op_sel_hi:[0,1]
	v_pk_mul_f32 v[6:7], v[36:37], v[6:7] op_sel_hi:[0,1]
	v_pk_mul_f32 v[4:5], v[36:37], v[4:5] op_sel_hi:[0,1]
	v_pk_mul_f32 v[2:3], v[36:37], v[2:3] op_sel_hi:[0,1]
	s_waitcnt vmcnt(0)
	v_pk_mul_f32 v[18:19], v[22:23], v[18:19]
	v_pk_mul_f32 v[20:21], v[24:25], v[20:21]
	v_pk_add_f32 v[24:25], v[50:51], 1.0 op_sel_hi:[1,0]
	v_pk_add_f32 v[22:23], v[52:53], 1.0 op_sel_hi:[1,0]
	v_pk_fma_f32 v[18:19], v[24:25], v[18:19], v[46:47]
	v_pk_fma_f32 v[20:21], v[22:23], v[20:21], v[48:49]
	v_cvt_pk_bf16_f32 v18, v18, v19
	v_lshl_add_u64 v[46:47], s[4:5], 0, v[30:31]
	v_cvt_pk_bf16_f32 v19, v20, v21
	global_store_dwordx2 v[28:29], v[18:19], off
	global_load_dwordx4 v[22:25], v[26:27], off offset:1024
	s_nop 0
	global_load_dwordx4 v[18:21], v[38:39], off offset:1024
	s_waitcnt vmcnt(0)
	v_pk_mul_f32 v[14:15], v[22:23], v[14:15]
	global_load_dwordx4 v[46:49], v[46:47], off
	v_pk_mul_f32 v[16:17], v[24:25], v[16:17]
	s_waitcnt vmcnt(0) lgkmcnt(0)
	v_pk_add_f32 v[24:25], v[46:47], 1.0 op_sel_hi:[1,0]
	v_pk_add_f32 v[22:23], v[48:49], 1.0 op_sel_hi:[1,0]
	v_pk_fma_f32 v[14:15], v[24:25], v[14:15], v[18:19]
	v_pk_fma_f32 v[16:17], v[22:23], v[16:17], v[20:21]
	v_cvt_pk_bf16_f32 v14, v14, v15
	v_lshl_add_u64 v[22:23], s[4:5], 0, v[32:33]
	v_cvt_pk_bf16_f32 v15, v16, v17
	global_store_dwordx2 v[28:29], v[14:15], off offset:512
	global_load_dwordx4 v[14:17], v[26:27], off offset:2048
	s_nop 0
	global_load_dwordx4 v[18:21], v[38:39], off offset:2048
	s_waitcnt vmcnt(0)
	v_pk_mul_f32 v[6:7], v[14:15], v[6:7]
	global_load_dwordx4 v[22:25], v[22:23], off
	v_pk_mul_f32 v[8:9], v[16:17], v[8:9]
	s_waitcnt vmcnt(0) lgkmcnt(0)
	v_pk_add_f32 v[16:17], v[22:23], 1.0 op_sel_hi:[1,0]
	v_pk_add_f32 v[14:15], v[24:25], 1.0 op_sel_hi:[1,0]
	v_pk_fma_f32 v[6:7], v[16:17], v[6:7], v[18:19]
	v_pk_fma_f32 v[8:9], v[14:15], v[8:9], v[20:21]
	v_cvt_pk_bf16_f32 v6, v6, v7
	v_lshl_add_u64 v[18:19], s[4:5], 0, v[34:35]
	v_cvt_pk_bf16_f32 v7, v8, v9
	global_store_dwordx2 v[28:29], v[6:7], off offset:1024
	global_load_dwordx4 v[6:9], v[26:27], off offset:3072
	s_nop 0
	global_load_dwordx4 v[14:17], v[38:39], off offset:3072
	s_waitcnt vmcnt(0)
	v_pk_mul_f32 v[2:3], v[6:7], v[2:3]
	global_load_dwordx4 v[18:21], v[18:19], off
	v_pk_mul_f32 v[4:5], v[8:9], v[4:5]
	s_waitcnt vmcnt(0) lgkmcnt(0)
	v_pk_add_f32 v[8:9], v[18:19], 1.0 op_sel_hi:[1,0]
	v_pk_add_f32 v[6:7], v[20:21], 1.0 op_sel_hi:[1,0]
	v_pk_fma_f32 v[2:3], v[8:9], v[2:3], v[14:15]
	v_pk_fma_f32 v[4:5], v[6:7], v[4:5], v[16:17]
	v_cvt_pk_bf16_f32 v2, v2, v3
	s_nop 0
	v_cvt_pk_bf16_f32 v3, v4, v5
	global_store_dwordx2 v[28:29], v[2:3], off offset:1536
	v_lshl_add_u64 v[28:29], v[28:29], 0, s[28:29]
	s_cbranch_scc0 .LBB0_1592
